# speedup vs baseline: 1.0303x; 1.0090x over previous
; __device__ void convert_weights(const Params& p, int layer, char* smem) {
;     ...
;       for (int e = tid; e < 4096; e += 256) {
;         int idx = v * 4096 + e;
;         int t = (idx >> 7) & 127, s = idx & 127;
;         float w = p.gm_w_s[(size_t)layer * 65536 + idx];
;         Ws_bf[idx] = (s <= t) ? f2bf(w) : (u16)0;
;       }
.LBB0_34:
	v_add_u32_e32 v7, s50, v5
	v_bfe_u32 v7, v7, 7, 7
	v_cmp_le_u32_e32 vcc, v14, v7
	v_mov_b32_e32 v7, 0
	s_and_saveexec_b64 s[40:41], vcc
	s_cbranch_execz .LBB0_33
	global_load_dword v7, v[8:9], off
	s_waitcnt vmcnt(0)
	v_cvt_pk_bf16_f32 v7, 0, v7
	v_lshrrev_b32_e32 v7, 16, v7
	s_branch .LBB0_33

; __device__ __forceinline__ unsigned pack2(float a, float b) { return (unsigned)f2bf(a) | ((unsigned)f2bf(b) << 16); }
; __device__ void convert_weights(const Params& p, int layer, char* smem) {
;     ...
;     __syncthreads();
; #pragma unroll
;     for (int i = 0; i < 4; ++i) {
;       int kk = (tid >> 4) + 16 * i, nn = (tid & 15) * 4;
;       float4 v = *reinterpret_cast<const float4*>(src + (size_t)(kt * 64 + kk) * N + nt * 64 + nn);
;       tile[kk * 65 + nn + 0] = v.x; tile[kk * 65 + nn + 1] = v.y;
;       tile[kk * 65 + nn + 2] = v.z; tile[kk * 65 + nn + 3] = v.w;
;     }
;     __syncthreads();
; #pragma unroll
;     for (int i = 0; i < 2; ++i) {
;       int nn = (tid >> 3) + 32 * i, kk0 = (tid & 7) * 8;
;       uint4 o;
;       o.x = pack2(tile[(kk0 + 0) * 65 + nn], tile[(kk0 + 1) * 65 + nn]);
;       o.y = pack2(tile[(kk0 + 2) * 65 + nn], tile[(kk0 + 3) * 65 + nn]);
;       o.z = pack2(tile[(kk0 + 4) * 65 + nn], tile[(kk0 + 5) * 65 + nn]);
;       o.w = pack2(tile[(kk0 + 6) * 65 + nn], tile[(kk0 + 7) * 65 + nn]);
;       *reinterpret_cast<uint4*>(dst + (size_t)(nt * 64 + nn) * K + kt * 64 + kk0) = o;
;     }
.LBB0_45:
	s_andn2_b64 vcc, exec, s[40:41]
	s_cbranch_vccnz .LBB0_27
	s_load_dwordx2 s[42:43], s[42:43], 0x0
	s_lshl_b32 s46, s56, 6
	s_ashr_i32 s47, s46, 31
	s_lshl_b32 s40, s55, 6
	s_lshl_b64 s[60:61], s[46:47], 2
	s_waitcnt lgkmcnt(0)
	s_add_u32 s42, s42, s60
	v_add_u32_e32 v5, s40, v12
	s_addc_u32 s43, s43, s61
	v_add_u32_e32 v7, 16, v5
	v_lshl_add_u64 v[34:35], s[42:43], 0, v[2:3]
	v_mad_i64_i32 v[8:9], s[42:43], s44, v5, 0
	v_mad_i64_i32 v[10:11], s[42:43], s44, v7, 0
	v_lshl_add_u64 v[8:9], v[8:9], 2, v[34:35]
	v_lshl_add_u64 v[26:27], v[10:11], 2, v[34:35]
	s_barrier
	global_load_dwordx4 v[8:11], v[8:9], off
	s_nop 0
	global_load_dwordx4 v[26:29], v[26:27], off
	v_add_u32_e32 v7, 32, v5
	v_mad_i64_i32 v[30:31], s[42:43], s44, v7, 0
	v_lshl_add_u64 v[30:31], v[30:31], 2, v[34:35]
	v_add_u32_e32 v5, 48, v5
	global_load_dwordx4 v[30:33], v[30:31], off
	v_mad_i64_i32 v[36:37], s[42:43], s44, v5, 0
	v_lshl_add_u64 v[34:35], v[36:37], 2, v[34:35]
	global_load_dwordx4 v[34:37], v[34:35], off
	v_add_u32_e32 v5, s46, v13
	v_ashrrev_i32_e32 v25, 31, v5
	v_mul_lo_u32 v42, s39, v5
	v_mad_u64_u32 v[38:39], s[42:43], s38, v5, 0
	v_add_u32_e32 v5, 32, v5
	v_ashrrev_i32_e32 v43, 31, v5
	s_ashr_i32 s41, s40, 31
	v_mul_lo_u32 v25, s38, v25
	v_mul_lo_u32 v44, s39, v5
	v_mad_u64_u32 v[40:41], s[42:43], s38, v5, 0
	v_mul_lo_u32 v5, s38, v43
	s_lshl_b64 s[38:39], s[40:41], 1
	s_add_u32 s36, s36, s38
	v_mov_b32_e32 v7, v3
	s_addc_u32 s37, s37, s39
	v_add3_u32 v39, v39, v25, v42
	v_add3_u32 v41, v41, v5, v44
	v_lshl_add_u64 v[42:43], s[36:37], 0, v[6:7]
	v_lshl_add_u64 v[38:39], v[38:39], 1, v[42:43]
	v_lshl_add_u64 v[40:41], v[40:41], 1, v[42:43]
	s_waitcnt vmcnt(3)
	ds_write2_b32 v16, v8, v9 offset1:1
	ds_write2_b32 v16, v10, v11 offset0:2 offset1:3
	s_waitcnt vmcnt(2)
	ds_write2_b32 v17, v26, v27 offset1:1
	ds_write2_b32 v18, v28, v29 offset1:1
	s_waitcnt vmcnt(1)
	ds_write2_b32 v19, v30, v31 offset1:1
	ds_write2_b32 v20, v32, v33 offset1:1
	s_waitcnt vmcnt(0)
	ds_write2_b32 v21, v34, v35 offset1:1
	ds_write2_b32 v22, v36, v37 offset1:1
	s_waitcnt lgkmcnt(0)
	s_barrier
	ds_read2_b32 v[26:27], v15 offset1:32
	ds_read2_b32 v[28:29], v15 offset0:65 offset1:97
	ds_read2_b32 v[30:31], v15 offset0:130 offset1:162
	ds_read2_b32 v[32:33], v15 offset0:195 offset1:227
	ds_read2_b32 v[34:35], v23 offset0:4 offset1:36
	ds_read2_b32 v[36:37], v23 offset0:69 offset1:101
	ds_read2_b32 v[42:43], v23 offset0:134 offset1:166
	ds_read2_b32 v[44:45], v23 offset0:199 offset1:231
	s_waitcnt lgkmcnt(7)
	s_waitcnt lgkmcnt(4)
	s_waitcnt lgkmcnt(3)
	s_waitcnt lgkmcnt(0)
	v_cvt_pk_bf16_f32 v7, 0, v26
	v_cvt_pk_bf16_f32 v8, 0, v32
	v_cvt_pk_bf16_f32 v9, 0, v28
	v_cvt_pk_bf16_f32 v26, 0, v34
	v_cvt_pk_bf16_f32 v11, 0, v44
	v_cvt_pk_bf16_f32 v25, 0, v36
	v_cvt_pk_bf16_f32 v5, 0, v30
	v_cvt_pk_bf16_f32 v10, 0, v42
	v_and_b32_e32 v8, 0xffff0000, v8
	v_and_b32_e32 v28, 0xffff0000, v9
	v_and_b32_e32 v11, 0xffff0000, v11
	v_and_b32_e32 v25, 0xffff0000, v25
	v_or_b32_sdwa v9, v8, v5 dst_sel:DWORD dst_unused:UNUSED_PAD src0_sel:DWORD src1_sel:WORD_1
	v_or_b32_sdwa v8, v28, v7 dst_sel:DWORD dst_unused:UNUSED_PAD src0_sel:DWORD src1_sel:WORD_1
	v_or_b32_sdwa v11, v11, v10 dst_sel:DWORD dst_unused:UNUSED_PAD src0_sel:DWORD src1_sel:WORD_1
	v_or_b32_sdwa v10, v25, v26 dst_sel:DWORD dst_unused:UNUSED_PAD src0_sel:DWORD src1_sel:WORD_1
	global_store_dwordx4 v[38:39], v[8:11], off
	s_nop 1
	v_cvt_pk_bf16_f32 v8, 0, v33
	s_nop 0
	v_cvt_pk_bf16_f32 v9, 0, v29
	v_cvt_pk_bf16_f32 v5, 0, v27
	v_cvt_pk_bf16_f32 v7, 0, v31
	v_and_b32_e32 v8, 0xffff0000, v8
	v_and_b32_e32 v10, 0xffff0000, v9
	v_or_b32_sdwa v9, v8, v7 dst_sel:DWORD dst_unused:UNUSED_PAD src0_sel:DWORD src1_sel:WORD_1
	v_or_b32_sdwa v8, v10, v5 dst_sel:DWORD dst_unused:UNUSED_PAD src0_sel:DWORD src1_sel:WORD_1
	v_cvt_pk_bf16_f32 v10, 0, v45
	v_cvt_pk_bf16_f32 v11, 0, v37
	v_cvt_pk_bf16_f32 v7, 0, v35
	v_cvt_pk_bf16_f32 v5, 0, v43
	v_and_b32_e32 v10, 0xffff0000, v10
	v_and_b32_e32 v25, 0xffff0000, v11
	v_or_b32_sdwa v11, v10, v5 dst_sel:DWORD dst_unused:UNUSED_PAD src0_sel:DWORD src1_sel:WORD_1
	v_or_b32_sdwa v10, v25, v7 dst_sel:DWORD dst_unused:UNUSED_PAD src0_sel:DWORD src1_sel:WORD_1
	global_store_dwordx4 v[40:41], v[8:11], off
	s_branch .LBB0_27

; __device__ __forceinline__ unsigned pack2(float a, float b) { return (unsigned)f2bf(a) | ((unsigned)f2bf(b) << 16); }
; __device__ __forceinline__ float bflo(unsigned w) { return __uint_as_float(w << 16); }
; __device__ void norm_phase(const Params& p, int layer) {
;     ...
;   for (int r2 = gw; r2 < NTOK / 2; r2 += nw) {
;     const int row = r2 * 2 + sub;
;     const size_t rbase = (size_t)row * DM + l32 * 4;
;     float4 xv[8];
;     if (layer < 0) {
; #pragma unroll
;       for (int i = 0; i < 8; ++i) xv[i] = *reinterpret_cast<const float4*>(p.x + rbase + i * 128);
;     } else {
;       const float* xr = (layer == 0) ? p.x : p.out;
;       float4 ov[8];
;       float ss = 0.f;
; #pragma unroll
;       for (int i = 0; i < 8; ++i) {
;         {
;           uint2 ob = *reinterpret_cast<const uint2*>(OUTB + rbase + i * 128);
;           ov[i] = make_float4(bflo(ob.x), bfhi(ob.x), bflo(ob.y), bfhi(ob.y));
;         }
;         xv[i] = *reinterpret_cast<const float4*>(xr + rbase + i * 128);
;       }
; #pragma unroll
;       for (int i = 0; i < 8; ++i) ss += ov[i].x * ov[i].x + ov[i].y * ov[i].y + ov[i].z * ov[i].z + ov[i].w * ov[i].w;
;       ss = half_wave_sum(ss);
;       float rstd = rsqrtf(ss * (1.f / 1024.f) + 1e-6f);
; #pragma unroll
;       for (int i = 0; i < 8; ++i) {
;         float4 g = *reinterpret_cast<const float4*>(p.g_post + (size_t)layer * DM + l32 * 4 + i * 128);
;         xv[i].x += ov[i].x * rstd * g.x;
;         xv[i].y += ov[i].y * rstd * g.y;
;         xv[i].z += ov[i].z * rstd * g.z;
;         xv[i].w += ov[i].w * rstd * g.w;
;         *reinterpret_cast<float4*>(p.out + rbase + i * 128) = xv[i];
;       }
;     }
;     const int nl = layer + 1;
;     if (nl < 4) {
;       float ss = 0.f;
; #pragma unroll
;       for (int i = 0; i < 8; ++i) ss += xv[i].x * xv[i].x + xv[i].y * xv[i].y + xv[i].z * xv[i].z + xv[i].w * xv[i].w;
;       ss = half_wave_sum(ss);
;       float rstd = rsqrtf(ss * (1.f / 1024.f) + 1e-6f);
; #pragma unroll
;       for (int i = 0; i < 8; ++i) {
;         float4 g = *reinterpret_cast<const float4*>(p.g_pre + (size_t)nl * DM + l32 * 4 + i * 128);
;         uint2 o;
;         o.x = pack2(xv[i].x * rstd * g.x, xv[i].y * rstd * g.y);
;         o.y = pack2(xv[i].z * rstd * g.z, xv[i].w * rstd * g.w);
;         *reinterpret_cast<uint2*>(H + rbase + i * 128) = o;
;       }
.LBB0_49:
	v_ashrrev_i32_e32 v23, 31, v22
	v_lshlrev_b64 v[24:25], 10, v[22:23]
	v_or_b32_e32 v24, v24, v18
	v_lshl_add_u64 v[54:55], v[24:25], 2, s[10:11]
	global_load_dwordx4 v[34:37], v[54:55], off
	global_load_dwordx4 v[38:41], v[54:55], off offset:512
	global_load_dwordx4 v[42:45], v[54:55], off offset:1024
	global_load_dwordx4 v[46:49], v[54:55], off offset:1536
	global_load_dwordx4 v[14:17], v[54:55], off offset:2048
	global_load_dwordx4 v[10:13], v[54:55], off offset:2560
	global_load_dwordx4 v[6:9], v[54:55], off offset:3072
	global_load_dwordx4 v[2:5], v[54:55], off offset:3584
	global_load_dwordx4 v[50:53], v[20:21], off
	v_lshl_add_u64 v[24:25], v[24:25], 1, s[8:9]
	v_add_u32_e32 v1, s56, v1
	v_add_u32_e32 v22, s14, v22
	s_waitcnt vmcnt(8)
	v_mul_f32_e32 v23, v35, v35
	s_waitcnt vmcnt(7)
	v_mul_f32_e32 v26, v39, v39
	s_waitcnt vmcnt(6)
	v_mov_b32_e32 v56, v43
	s_waitcnt vmcnt(5)
	v_mov_b32_e32 v57, v47
	v_mov_b32_e32 v54, v42
	v_mov_b32_e32 v55, v46
	v_fmac_f32_e32 v23, v34, v34
	v_fmac_f32_e32 v26, v38, v38
	v_pk_mul_f32 v[56:57], v[56:57], v[56:57]
	v_mov_b32_e32 v58, v44
	v_mov_b32_e32 v59, v48
	s_waitcnt vmcnt(4)
	v_mov_b32_e32 v64, v15
	s_waitcnt vmcnt(3)
	v_mov_b32_e32 v65, v11
	v_fmac_f32_e32 v23, v36, v36
	v_fmac_f32_e32 v26, v40, v40
	v_pk_fma_f32 v[54:55], v[54:55], v[54:55], v[56:57]
	v_mov_b32_e32 v60, v45
	v_mov_b32_e32 v61, v49
	v_mov_b32_e32 v62, v14
	v_mov_b32_e32 v63, v10
	v_pk_mul_f32 v[64:65], v[64:65], v[64:65]
	v_fmac_f32_e32 v23, v37, v37
	v_fmac_f32_e32 v26, v41, v41
	v_pk_fma_f32 v[54:55], v[58:59], v[58:59], v[54:55]
	v_mov_b32_e32 v66, v16
	v_mov_b32_e32 v67, v12
	s_waitcnt vmcnt(2)
	v_mov_b32_e32 v72, v7
	s_waitcnt vmcnt(1)
	v_mov_b32_e32 v73, v3
	v_pk_fma_f32 v[56:57], v[62:63], v[62:63], v[64:65]
	v_add_f32_e32 v23, v23, v26
	v_pk_fma_f32 v[54:55], v[60:61], v[60:61], v[54:55]
	v_mov_b32_e32 v68, v17
	v_mov_b32_e32 v69, v13
	v_mov_b32_e32 v70, v6
	v_mov_b32_e32 v71, v2
	v_pk_mul_f32 v[72:73], v[72:73], v[72:73]
	v_pk_fma_f32 v[56:57], v[66:67], v[66:67], v[56:57]
	v_add_f32_e32 v23, v23, v54
	v_mov_b32_e32 v74, v8
	v_mov_b32_e32 v75, v4
	v_pk_fma_f32 v[62:63], v[70:71], v[70:71], v[72:73]
	v_pk_fma_f32 v[56:57], v[68:69], v[68:69], v[56:57]
	v_add_f32_e32 v23, v23, v55
	v_mov_b32_e32 v76, v9
	v_mov_b32_e32 v77, v5
	v_pk_fma_f32 v[58:59], v[74:75], v[74:75], v[62:63]
	v_add_f32_e32 v23, v23, v56
	v_pk_fma_f32 v[58:59], v[76:77], v[76:77], v[58:59]
	v_add_f32_e32 v23, v23, v57
	v_add_f32_e32 v23, v23, v58
	v_add_f32_e32 v23, v23, v59
	ds_bpermute_b32 v26, v19, v23
	s_waitcnt vmcnt(0)
	v_mov_b32_e32 v54, v50
	v_mov_b32_e32 v55, v52
	v_mov_b32_e32 v52, v51
	v_mov_b32_e32 v50, v34
	s_waitcnt lgkmcnt(0)
	v_add_f32_e32 v23, v23, v26
	ds_bpermute_b32 v26, v27, v23
	v_mov_b32_e32 v51, v36
	v_mov_b32_e32 v36, v35
	s_waitcnt lgkmcnt(0)
	v_add_f32_e32 v23, v23, v26
	ds_bpermute_b32 v26, v28, v23
	s_waitcnt lgkmcnt(0)
	v_add_f32_e32 v23, v23, v26
	ds_bpermute_b32 v26, v29, v23
	s_waitcnt lgkmcnt(0)
	v_add_f32_e32 v23, v23, v26
	ds_bpermute_b32 v26, v30, v23
	s_waitcnt lgkmcnt(0)
	v_add_f32_e32 v23, v23, v26
	v_fmamk_f32 v23, v23, 0x3a800000, v31
	v_mul_f32_e32 v26, 0x4b800000, v23
	v_cmp_gt_f32_e32 vcc, s15, v23
	s_nop 1
	v_cndmask_b32_e32 v23, v23, v26, vcc
	v_rsq_f32_e32 v23, v23
	s_nop 0
	v_mul_f32_e32 v26, 0x45800000, v23
	v_cndmask_b32_e32 v26, v23, v26, vcc
	v_pk_mul_f32 v[34:35], v[50:51], v[26:27] op_sel_hi:[1,0]
	v_pk_mul_f32 v[36:37], v[36:37], v[26:27] op_sel_hi:[1,0]
	v_pk_mul_f32 v[34:35], v[54:55], v[34:35]
	v_pk_mul_f32 v[36:37], v[52:53], v[36:37]
	v_cvt_pk_bf16_f32 v33, 0, v34
	v_cvt_pk_bf16_f32 v23, 0, v35
	v_cvt_pk_bf16_f32 v34, 0, v37
	v_cvt_pk_bf16_f32 v35, 0, v36
	v_and_b32_e32 v34, 0xffff0000, v34
	v_and_b32_e32 v36, 0xffff0000, v35
	v_or_b32_sdwa v35, v34, v23 dst_sel:DWORD dst_unused:UNUSED_PAD src0_sel:DWORD src1_sel:WORD_1
	v_or_b32_sdwa v34, v36, v33 dst_sel:DWORD dst_unused:UNUSED_PAD src0_sel:DWORD src1_sel:WORD_1
	global_store_dwordx2 v[24:25], v[34:35], off
	global_load_dwordx4 v[34:37], v[20:21], off offset:512
	v_mov_b32_e32 v50, v38
	v_mov_b32_e32 v51, v40
	v_mov_b32_e32 v40, v39
	v_pk_mul_f32 v[38:39], v[50:51], v[26:27] op_sel_hi:[1,0]
	v_pk_mul_f32 v[40:41], v[40:41], v[26:27] op_sel_hi:[1,0]
	v_cmp_lt_i32_e32 vcc, s21, v1
	s_or_b64 s[12:13], vcc, s[12:13]
	s_waitcnt vmcnt(0)
	v_mov_b32_e32 v50, v34
	v_mov_b32_e32 v51, v36
	v_mov_b32_e32 v36, v35
	v_pk_mul_f32 v[34:35], v[50:51], v[38:39]
	v_pk_mul_f32 v[36:37], v[36:37], v[40:41]
	v_cvt_pk_bf16_f32 v33, 0, v34
	v_cvt_pk_bf16_f32 v23, 0, v35
	v_cvt_pk_bf16_f32 v34, 0, v37
	v_cvt_pk_bf16_f32 v35, 0, v36
	v_and_b32_e32 v34, 0xffff0000, v34
	v_and_b32_e32 v36, 0xffff0000, v35
	v_or_b32_sdwa v35, v34, v23 dst_sel:DWORD dst_unused:UNUSED_PAD src0_sel:DWORD src1_sel:WORD_1
	v_or_b32_sdwa v34, v36, v33 dst_sel:DWORD dst_unused:UNUSED_PAD src0_sel:DWORD src1_sel:WORD_1
	global_store_dwordx2 v[24:25], v[34:35], off offset:256
	global_load_dwordx4 v[34:37], v[20:21], off offset:1024
	v_mov_b32_e32 v38, v42
	v_mov_b32_e32 v39, v44
	v_mov_b32_e32 v40, v43
	v_mov_b32_e32 v41, v45
	v_pk_mul_f32 v[38:39], v[38:39], v[26:27] op_sel_hi:[1,0]
	v_pk_mul_f32 v[40:41], v[40:41], v[26:27] op_sel_hi:[1,0]
	s_waitcnt vmcnt(0)
; __device__ __forceinline__ unsigned pack2(float a, float b) { return (unsigned)f2bf(a) | ((unsigned)f2bf(b) << 16); }
; __device__ void norm_phase(const Params& p, int layer) {
;     ...
; #pragma unroll
;       for (int i = 0; i < 8; ++i) {
;         float4 g = *reinterpret_cast<const float4*>(p.g_pre + (size_t)nl * DM + l32 * 4 + i * 128);
;         uint2 o;
;         o.x = pack2(xv[i].x * rstd * g.x, xv[i].y * rstd * g.y);
;         o.y = pack2(xv[i].z * rstd * g.z, xv[i].w * rstd * g.w);
;         *reinterpret_cast<uint2*>(H + rbase + i * 128) = o;
;       }
	v_mov_b32_e32 v42, v34
	v_mov_b32_e32 v43, v36
	v_mov_b32_e32 v36, v35
	v_pk_mul_f32 v[34:35], v[38:39], v[42:43]
	v_pk_mul_f32 v[36:37], v[40:41], v[36:37]
	v_cvt_pk_bf16_f32 v33, 0, v34
	v_cvt_pk_bf16_f32 v23, 0, v35
	v_cvt_pk_bf16_f32 v34, 0, v37
	v_cvt_pk_bf16_f32 v35, 0, v36
	v_and_b32_e32 v34, 0xffff0000, v34
	v_and_b32_e32 v36, 0xffff0000, v35
	v_or_b32_sdwa v35, v34, v23 dst_sel:DWORD dst_unused:UNUSED_PAD src0_sel:DWORD src1_sel:WORD_1
	v_or_b32_sdwa v34, v36, v33 dst_sel:DWORD dst_unused:UNUSED_PAD src0_sel:DWORD src1_sel:WORD_1
	global_store_dwordx2 v[24:25], v[34:35], off offset:512
	global_load_dwordx4 v[34:37], v[20:21], off offset:1536
	v_mov_b32_e32 v38, v46
	v_mov_b32_e32 v39, v48
	v_mov_b32_e32 v48, v47
	v_pk_mul_f32 v[38:39], v[38:39], v[26:27] op_sel_hi:[1,0]
	v_pk_mul_f32 v[40:41], v[48:49], v[26:27] op_sel_hi:[1,0]
	s_waitcnt vmcnt(0)
	v_mov_b32_e32 v42, v34
	v_mov_b32_e32 v43, v36
	v_mov_b32_e32 v36, v35
	v_pk_mul_f32 v[34:35], v[38:39], v[42:43]
	v_pk_mul_f32 v[36:37], v[40:41], v[36:37]
	v_cvt_pk_bf16_f32 v33, 0, v34
	v_cvt_pk_bf16_f32 v23, 0, v35
	v_cvt_pk_bf16_f32 v34, 0, v37
	v_cvt_pk_bf16_f32 v35, 0, v36
	v_and_b32_e32 v34, 0xffff0000, v34
	v_and_b32_e32 v36, 0xffff0000, v35
	v_or_b32_sdwa v35, v34, v23 dst_sel:DWORD dst_unused:UNUSED_PAD src0_sel:DWORD src1_sel:WORD_1
	v_or_b32_sdwa v34, v36, v33 dst_sel:DWORD dst_unused:UNUSED_PAD src0_sel:DWORD src1_sel:WORD_1
	global_store_dwordx2 v[24:25], v[34:35], off offset:768
	global_load_dwordx4 v[34:37], v[20:21], off offset:2048
	v_mov_b32_e32 v38, v14
	v_mov_b32_e32 v39, v16
	v_mov_b32_e32 v14, v15
	v_mov_b32_e32 v15, v17
	v_pk_mul_f32 v[16:17], v[38:39], v[26:27] op_sel_hi:[1,0]
	v_pk_mul_f32 v[14:15], v[14:15], v[26:27] op_sel_hi:[1,0]
	s_waitcnt vmcnt(0)
	v_mov_b32_e32 v39, v36
	v_mov_b32_e32 v36, v35
	v_mov_b32_e32 v38, v34
	v_pk_mul_f32 v[14:15], v[14:15], v[36:37]
	v_pk_mul_f32 v[16:17], v[16:17], v[38:39]
	v_cvt_pk_bf16_f32 v15, 0, v15
	v_cvt_pk_bf16_f32 v14, 0, v14
	v_cvt_pk_bf16_f32 v16, 0, v16
	v_cvt_pk_bf16_f32 v17, 0, v17
	v_and_b32_e32 v15, 0xffff0000, v15
	v_and_b32_e32 v14, 0xffff0000, v14
	v_or_b32_sdwa v15, v15, v17 dst_sel:DWORD dst_unused:UNUSED_PAD src0_sel:DWORD src1_sel:WORD_1
	v_or_b32_sdwa v14, v14, v16 dst_sel:DWORD dst_unused:UNUSED_PAD src0_sel:DWORD src1_sel:WORD_1
	global_store_dwordx2 v[24:25], v[14:15], off offset:1024
	global_load_dwordx4 v[14:17], v[20:21], off offset:2560
	v_mov_b32_e32 v34, v10
	v_mov_b32_e32 v35, v12
	v_mov_b32_e32 v12, v11
	v_pk_mul_f32 v[10:11], v[34:35], v[26:27] op_sel_hi:[1,0]
	v_pk_mul_f32 v[12:13], v[12:13], v[26:27] op_sel_hi:[1,0]
	s_waitcnt vmcnt(0)
	v_mov_b32_e32 v35, v16
	v_mov_b32_e32 v16, v15
	v_mov_b32_e32 v34, v14
	v_pk_mul_f32 v[12:13], v[12:13], v[16:17]
	v_pk_mul_f32 v[10:11], v[10:11], v[34:35]
	v_cvt_pk_bf16_f32 v13, 0, v13
	v_cvt_pk_bf16_f32 v12, 0, v12
	v_cvt_pk_bf16_f32 v10, 0, v10
	v_cvt_pk_bf16_f32 v11, 0, v11
	v_and_b32_e32 v13, 0xffff0000, v13
	v_and_b32_e32 v12, 0xffff0000, v12
	v_or_b32_sdwa v11, v13, v11 dst_sel:DWORD dst_unused:UNUSED_PAD src0_sel:DWORD src1_sel:WORD_1
	v_or_b32_sdwa v10, v12, v10 dst_sel:DWORD dst_unused:UNUSED_PAD src0_sel:DWORD src1_sel:WORD_1
	global_store_dwordx2 v[24:25], v[10:11], off offset:1280
	global_load_dwordx4 v[10:13], v[20:21], off offset:3072
	v_mov_b32_e32 v14, v6
	v_mov_b32_e32 v15, v8
	v_mov_b32_e32 v6, v7
	v_mov_b32_e32 v7, v9
	v_pk_mul_f32 v[8:9], v[14:15], v[26:27] op_sel_hi:[1,0]
	v_pk_mul_f32 v[6:7], v[6:7], v[26:27] op_sel_hi:[1,0]
	s_waitcnt vmcnt(0)
	v_mov_b32_e32 v15, v12
	v_mov_b32_e32 v12, v11
	v_mov_b32_e32 v14, v10
	v_pk_mul_f32 v[6:7], v[6:7], v[12:13]
	v_pk_mul_f32 v[8:9], v[8:9], v[14:15]
	v_cvt_pk_bf16_f32 v7, 0, v7
	v_cvt_pk_bf16_f32 v6, 0, v6
	v_cvt_pk_bf16_f32 v8, 0, v8
	v_cvt_pk_bf16_f32 v9, 0, v9
	v_and_b32_e32 v7, 0xffff0000, v7
	v_and_b32_e32 v6, 0xffff0000, v6
	v_or_b32_sdwa v7, v7, v9 dst_sel:DWORD dst_unused:UNUSED_PAD src0_sel:DWORD src1_sel:WORD_1
	v_or_b32_sdwa v6, v6, v8 dst_sel:DWORD dst_unused:UNUSED_PAD src0_sel:DWORD src1_sel:WORD_1
	global_store_dwordx2 v[24:25], v[6:7], off offset:1536
	global_load_dwordx4 v[6:9], v[20:21], off offset:3584
	v_mov_b32_e32 v10, v2
	v_mov_b32_e32 v11, v4
	v_mov_b32_e32 v4, v3
	v_pk_mul_f32 v[2:3], v[10:11], v[26:27] op_sel_hi:[1,0]
	v_pk_mul_f32 v[4:5], v[4:5], v[26:27] op_sel_hi:[1,0]
	s_waitcnt vmcnt(0)
	v_mov_b32_e32 v11, v8
	v_mov_b32_e32 v8, v7
	v_mov_b32_e32 v10, v6
	v_pk_mul_f32 v[4:5], v[4:5], v[8:9]
	v_pk_mul_f32 v[2:3], v[2:3], v[10:11]
	v_cvt_pk_bf16_f32 v5, 0, v5
	v_cvt_pk_bf16_f32 v4, 0, v4
	v_cvt_pk_bf16_f32 v2, 0, v2
	v_cvt_pk_bf16_f32 v3, 0, v3
	v_and_b32_e32 v5, 0xffff0000, v5
	v_and_b32_e32 v4, 0xffff0000, v4
	v_or_b32_sdwa v3, v5, v3 dst_sel:DWORD dst_unused:UNUSED_PAD src0_sel:DWORD src1_sel:WORD_1
	v_or_b32_sdwa v2, v4, v2 dst_sel:DWORD dst_unused:UNUSED_PAD src0_sel:DWORD src1_sel:WORD_1
	global_store_dwordx2 v[24:25], v[2:3], off offset:1792
	s_andn2_b64 exec, exec, s[12:13]
	s_cbranch_execnz .LBB0_49

; template <int WM, int WN>
; __device__ __forceinline__ void store_tile_bf16(const f32x4 (&acc)[WM][WN], u16* dst, int ld, char* smem) {
;   constexpr int BM = 32 * WM, BN = 32 * WN, STR = BN + 8;
;   const int tid = opaque_tid(), lane = tid & 63, wid = tid >> 6;
;   const int wr = wid >> 1, wc = wid & 1, fr = lane & 15, fq = lane >> 4;
;   u16* T = reinterpret_cast<u16*>(smem);
; #pragma unroll
;   for (int m = 0; m < WM; ++m)
; #pragma unroll
;     for (int n = 0; n < WN; ++n)
; #pragma unroll
;       for (int j = 0; j < 4; ++j)
;         T[(wr * 16 * WM + m * 16 + fq * 4 + j) * STR + wc * 16 * WN + n * 16 + fr] = f2bf(acc[m][n][j]);
;   __syncthreads();
.LBB0_102:
	v_mov_b32_e32 v64, v232
	v_lshrrev_b32_e32 v66, 2, v64
	s_waitcnt lgkmcnt(0)
	v_lshrrev_b32_e32 v65, 1, v64
	v_and_b32_e32 v66, 12, v66
	v_and_or_b32 v65, v65, s48, v66
	v_and_b32_e32 v66, 0x4f, v64
	v_mul_lo_u32 v65, v65, s50
	v_cvt_pk_bf16_f32 v44, 0, v44
	v_lshl_add_u32 v65, v66, 1, v65
	ds_write_b16_d16_hi v65, v44
	v_cvt_pk_bf16_f32 v44, 0, v45
	ds_write_b16_d16_hi v65, v44 offset:272
	v_cvt_pk_bf16_f32 v44, 0, v46
	ds_write_b16_d16_hi v65, v44 offset:544
	v_cvt_pk_bf16_f32 v44, 0, v47
	ds_write_b16_d16_hi v65, v44 offset:816
	v_cvt_pk_bf16_f32 v40, 0, v40
	ds_write_b16_d16_hi v65, v40 offset:32
	v_cvt_pk_bf16_f32 v40, 0, v41
	ds_write_b16_d16_hi v65, v40 offset:304
	v_cvt_pk_bf16_f32 v40, 0, v42
	ds_write_b16_d16_hi v65, v40 offset:576
	v_cvt_pk_bf16_f32 v40, 0, v43
	ds_write_b16_d16_hi v65, v40 offset:848
	v_cvt_pk_bf16_f32 v36, 0, v36
	ds_write_b16_d16_hi v65, v36 offset:64
	v_cvt_pk_bf16_f32 v36, 0, v37
	ds_write_b16_d16_hi v65, v36 offset:336
	v_cvt_pk_bf16_f32 v36, 0, v38
	ds_write_b16_d16_hi v65, v36 offset:608
	v_cvt_pk_bf16_f32 v36, 0, v39
	ds_write_b16_d16_hi v65, v36 offset:880
	v_cvt_pk_bf16_f32 v32, 0, v32
	ds_write_b16_d16_hi v65, v32 offset:96
	v_cvt_pk_bf16_f32 v32, 0, v33
	ds_write_b16_d16_hi v65, v32 offset:368
	v_cvt_pk_bf16_f32 v32, 0, v34
	ds_write_b16_d16_hi v65, v32 offset:640
	v_cvt_pk_bf16_f32 v32, 0, v35
	ds_write_b16_d16_hi v65, v32 offset:912
	v_cvt_pk_bf16_f32 v28, 0, v28
	ds_write_b16_d16_hi v65, v28 offset:4352
	v_cvt_pk_bf16_f32 v28, 0, v29
	ds_write_b16_d16_hi v65, v28 offset:4624
	v_cvt_pk_bf16_f32 v28, 0, v30
	ds_write_b16_d16_hi v65, v28 offset:4896
	v_cvt_pk_bf16_f32 v28, 0, v31
	ds_write_b16_d16_hi v65, v28 offset:5168
	v_cvt_pk_bf16_f32 v24, 0, v24
	ds_write_b16_d16_hi v65, v24 offset:4384
	v_cvt_pk_bf16_f32 v24, 0, v25
	ds_write_b16_d16_hi v65, v24 offset:4656
	v_cvt_pk_bf16_f32 v24, 0, v26
	ds_write_b16_d16_hi v65, v24 offset:4928
	v_cvt_pk_bf16_f32 v24, 0, v27
	ds_write_b16_d16_hi v65, v24 offset:5200
	v_cvt_pk_bf16_f32 v20, 0, v20
	ds_write_b16_d16_hi v65, v20 offset:4416
	v_cvt_pk_bf16_f32 v20, 0, v21
	ds_write_b16_d16_hi v65, v20 offset:4688
	v_cvt_pk_bf16_f32 v20, 0, v22
	ds_write_b16_d16_hi v65, v20 offset:4960
	v_cvt_pk_bf16_f32 v20, 0, v23
	ds_write_b16_d16_hi v65, v20 offset:5232
	v_cvt_pk_bf16_f32 v16, 0, v16
	ds_write_b16_d16_hi v65, v16 offset:4448
	v_cvt_pk_bf16_f32 v16, 0, v17
	ds_write_b16_d16_hi v65, v16 offset:4720
	v_cvt_pk_bf16_f32 v16, 0, v18
	ds_write_b16_d16_hi v65, v16 offset:4992
	v_cvt_pk_bf16_f32 v16, 0, v19
	ds_write_b16_d16_hi v65, v16 offset:5264
	v_cvt_pk_bf16_f32 v12, 0, v12
	ds_write_b16_d16_hi v65, v12 offset:8704
	v_cvt_pk_bf16_f32 v12, 0, v13
	ds_write_b16_d16_hi v65, v12 offset:8976
	v_cvt_pk_bf16_f32 v12, 0, v14
	ds_write_b16_d16_hi v65, v12 offset:9248
	v_cvt_pk_bf16_f32 v12, 0, v15
	ds_write_b16_d16_hi v65, v12 offset:9520
	v_cvt_pk_bf16_f32 v8, 0, v8
	ds_write_b16_d16_hi v65, v8 offset:8736
	v_cvt_pk_bf16_f32 v8, 0, v9
	ds_write_b16_d16_hi v65, v8 offset:9008
	v_cvt_pk_bf16_f32 v8, 0, v10
	ds_write_b16_d16_hi v65, v8 offset:9280
	v_cvt_pk_bf16_f32 v8, 0, v11
	ds_write_b16_d16_hi v65, v8 offset:9552
	v_cvt_pk_bf16_f32 v4, 0, v4
	ds_write_b16_d16_hi v65, v4 offset:8768
	v_cvt_pk_bf16_f32 v4, 0, v5
	ds_write_b16_d16_hi v65, v4 offset:9040
	v_cvt_pk_bf16_f32 v4, 0, v6
	ds_write_b16_d16_hi v65, v4 offset:9312
	v_cvt_pk_bf16_f32 v4, 0, v7
	ds_write_b16_d16_hi v65, v4 offset:9584
	v_cvt_pk_bf16_f32 v0, 0, v0
	ds_write_b16_d16_hi v65, v0 offset:8800
	v_cvt_pk_bf16_f32 v0, 0, v1
	ds_write_b16_d16_hi v65, v0 offset:9072
	v_cvt_pk_bf16_f32 v0, 0, v2
	ds_write_b16_d16_hi v65, v0 offset:9344
	v_cvt_pk_bf16_f32 v0, 0, v3
	ds_write_b16_d16_hi v65, v0 offset:9616
	v_cvt_pk_bf16_f32 v0, 0, v60
	ds_write_b16_d16_hi v65, v0 offset:13056
	v_cvt_pk_bf16_f32 v0, 0, v61
	ds_write_b16_d16_hi v65, v0 offset:13328
	v_cvt_pk_bf16_f32 v0, 0, v62
	ds_write_b16_d16_hi v65, v0 offset:13600
	v_cvt_pk_bf16_f32 v0, 0, v63
	ds_write_b16_d16_hi v65, v0 offset:13872
	v_cvt_pk_bf16_f32 v0, 0, v56
	ds_write_b16_d16_hi v65, v0 offset:13088
	v_cvt_pk_bf16_f32 v0, 0, v57
	ds_write_b16_d16_hi v65, v0 offset:13360
	v_cvt_pk_bf16_f32 v0, 0, v58
	ds_write_b16_d16_hi v65, v0 offset:13632
	v_cvt_pk_bf16_f32 v0, 0, v59
	ds_write_b16_d16_hi v65, v0 offset:13904
	v_cvt_pk_bf16_f32 v0, 0, v52
	ds_write_b16_d16_hi v65, v0 offset:13120
	v_cvt_pk_bf16_f32 v0, 0, v53
	ds_write_b16_d16_hi v65, v0 offset:13392
	v_cvt_pk_bf16_f32 v0, 0, v54
	ds_write_b16_d16_hi v65, v0 offset:13664
	v_cvt_pk_bf16_f32 v0, 0, v55
	ds_write_b16_d16_hi v65, v0 offset:13936
	v_cvt_pk_bf16_f32 v0, 0, v48
	ds_write_b16_d16_hi v65, v0 offset:13152
	v_cvt_pk_bf16_f32 v0, 0, v49
	ds_write_b16_d16_hi v65, v0 offset:13424
	v_cvt_pk_bf16_f32 v0, 0, v50
	ds_write_b16_d16_hi v65, v0 offset:13696
	s_lshl_b32 s12, s12, 7
	s_mul_hi_i32 s6, s10, 0x130000
	s_mul_i32 s10, s10, 0x130000
	v_cvt_pk_bf16_f32 v0, 0, v51
	s_add_u32 s14, s37, s10
	ds_write_b16_d16_hi v65, v0 offset:13968
	v_ashrrev_i32_e32 v0, 31, v64
	s_addc_u32 s6, s38, s6
	s_ashr_i32 s13, s12, 31
	v_lshrrev_b32_e32 v0, 28, v0
	s_lshl_b64 s[10:11], s[12:13], 1
	v_add_u32_e32 v0, v64, v0
	s_add_u32 s10, s14, s10
	v_ashrrev_i32_e32 v6, 4, v0
	v_and_b32_e32 v0, -16, v0
	s_addc_u32 s11, s6, s11
	v_sub_u32_e32 v0, v64, v0
	v_lshlrev_b32_e32 v4, 3, v0
	v_mov_b64_e32 v[8:9], s[10:11]
	v_mul_lo_u32 v1, v6, s50
	v_ashrrev_i32_e32 v5, 31, v4
	v_mad_i64_i32 v[6:7], s[10:11], v6, s24, v[8:9]
	v_lshl_add_u64 v[10:11], v[4:5], 1, v[6:7]
	v_add_u32_e32 v4, 0x100, v64
	v_ashrrev_i32_e32 v5, 31, v4
	v_lshrrev_b32_e32 v5, 28, v5
	v_lshl_add_u32 v0, v0, 4, v1
	v_add_u32_e32 v5, v4, v5
	s_waitcnt lgkmcnt(0)
	s_barrier
; template <int WM, int WN>
; __device__ __forceinline__ void store_tile_bf16(const f32x4 (&acc)[WM][WN], u16* dst, int ld, char* smem) {
;     ...
;   __syncthreads();
;   constexpr int CPR = BN / 8;
; #pragma unroll
;   for (int i = 0; i < BM * CPR / 256; ++i) {
;     int q = tid + 256 * i, row = q / CPR, c = q % CPR;
;     uint4 v = *reinterpret_cast<const uint4*>(T + row * STR + c * 8);
;     *reinterpret_cast<uint4*>(dst + (size_t)row * ld + c * 8) = v;
;   }
	ds_read_b128 v[0:3], v0
	v_ashrrev_i32_e32 v12, 4, v5
	v_and_b32_e32 v5, -16, v5
	v_sub_u32_e32 v13, v4, v5
	v_mul_lo_u32 v4, v12, s50
	v_lshl_add_u32 v4, v13, 4, v4
	ds_read_b128 v[4:7], v4
	s_waitcnt lgkmcnt(1)
	global_store_dwordx4 v[10:11], v[0:3], off
	s_add_i32 s51, s51, s61
	s_cmp_lt_i32 s51, s47
	v_lshlrev_b32_e32 v0, 3, v13
	v_ashrrev_i32_e32 v1, 31, v0
	v_mad_i64_i32 v[2:3], s[10:11], v12, s24, v[8:9]
	v_lshl_add_u64 v[0:1], v[0:1], 1, v[2:3]
	s_waitcnt lgkmcnt(0)
	global_store_dwordx4 v[0:1], v[4:7], off
	v_add_u32_e32 v0, 0x200, v64
	v_ashrrev_i32_e32 v1, 31, v0
	v_lshrrev_b32_e32 v1, 28, v1
	v_add_u32_e32 v1, v0, v1
	v_ashrrev_i32_e32 v6, 4, v1
	v_and_b32_e32 v1, -16, v1
	v_sub_u32_e32 v0, v0, v1
	v_lshlrev_b32_e32 v4, 3, v0
	v_mul_lo_u32 v1, v6, s50
	v_ashrrev_i32_e32 v5, 31, v4
	v_mad_i64_i32 v[6:7], s[10:11], v6, s24, v[8:9]
	v_lshl_add_u64 v[10:11], v[4:5], 1, v[6:7]
	v_add_u32_e32 v4, 0x300, v64
	v_ashrrev_i32_e32 v5, 31, v4
	v_lshrrev_b32_e32 v5, 28, v5
	v_lshl_add_u32 v0, v0, 4, v1
	v_add_u32_e32 v5, v4, v5
	ds_read_b128 v[0:3], v0
	v_ashrrev_i32_e32 v12, 4, v5
	v_and_b32_e32 v5, -16, v5
	v_sub_u32_e32 v13, v4, v5
	v_mul_lo_u32 v4, v12, s50
	v_lshl_add_u32 v4, v13, 4, v4
	ds_read_b128 v[4:7], v4
	s_waitcnt lgkmcnt(1)
	global_store_dwordx4 v[10:11], v[0:3], off
	s_nop 1
	v_lshlrev_b32_e32 v0, 3, v13
	v_ashrrev_i32_e32 v1, 31, v0
	v_mad_i64_i32 v[2:3], s[10:11], v12, s24, v[8:9]
	v_lshl_add_u64 v[0:1], v[0:1], 1, v[2:3]
	s_waitcnt lgkmcnt(0)
	global_store_dwordx4 v[0:1], v[4:7], off
	v_add_u32_e32 v0, 0x400, v64
	v_ashrrev_i32_e32 v1, 31, v0
	v_lshrrev_b32_e32 v1, 28, v1
	v_add_u32_e32 v1, v0, v1
	v_ashrrev_i32_e32 v6, 4, v1
	v_and_b32_e32 v1, -16, v1
	v_sub_u32_e32 v0, v0, v1
	v_lshlrev_b32_e32 v4, 3, v0
	v_mul_lo_u32 v1, v6, s50
	v_ashrrev_i32_e32 v5, 31, v4
	v_mad_i64_i32 v[6:7], s[10:11], v6, s24, v[8:9]
	v_lshl_add_u64 v[10:11], v[4:5], 1, v[6:7]
	v_add_u32_e32 v4, 0x500, v64
	v_ashrrev_i32_e32 v5, 31, v4
	v_lshrrev_b32_e32 v5, 28, v5
	v_lshl_add_u32 v0, v0, 4, v1
	v_add_u32_e32 v5, v4, v5
	ds_read_b128 v[0:3], v0
	v_ashrrev_i32_e32 v12, 4, v5
	v_and_b32_e32 v5, -16, v5
	v_sub_u32_e32 v13, v4, v5
	v_mul_lo_u32 v4, v12, s50
	v_lshl_add_u32 v4, v13, 4, v4
	ds_read_b128 v[4:7], v4
	s_waitcnt lgkmcnt(1)
	global_store_dwordx4 v[10:11], v[0:3], off
	s_nop 1
	v_lshlrev_b32_e32 v0, 3, v13
	v_ashrrev_i32_e32 v1, 31, v0
	v_mad_i64_i32 v[2:3], s[10:11], v12, s24, v[8:9]
	v_lshl_add_u64 v[0:1], v[0:1], 1, v[2:3]
	s_waitcnt lgkmcnt(0)
	global_store_dwordx4 v[0:1], v[4:7], off
	v_add_u32_e32 v0, 0x600, v64
	v_ashrrev_i32_e32 v1, 31, v0
	v_lshrrev_b32_e32 v1, 28, v1
	v_add_u32_e32 v1, v0, v1
	v_ashrrev_i32_e32 v6, 4, v1
	v_and_b32_e32 v1, -16, v1
	v_sub_u32_e32 v0, v0, v1
	v_lshlrev_b32_e32 v4, 3, v0
	v_mul_lo_u32 v1, v6, s50
	v_ashrrev_i32_e32 v5, 31, v4
	v_mad_i64_i32 v[6:7], s[10:11], v6, s24, v[8:9]
	v_lshl_add_u64 v[10:11], v[4:5], 1, v[6:7]
	v_add_u32_e32 v4, 0x700, v64
	v_ashrrev_i32_e32 v5, 31, v4
	v_lshrrev_b32_e32 v5, 28, v5
	v_lshl_add_u32 v0, v0, 4, v1
	v_add_u32_e32 v5, v4, v5
	ds_read_b128 v[0:3], v0
	v_ashrrev_i32_e32 v12, 4, v5
	v_and_b32_e32 v5, -16, v5
	v_sub_u32_e32 v13, v4, v5
	v_mul_lo_u32 v4, v12, s50
	v_lshl_add_u32 v4, v13, 4, v4
	ds_read_b128 v[4:7], v4
	s_waitcnt lgkmcnt(1)
	global_store_dwordx4 v[10:11], v[0:3], off
	s_nop 1
	v_lshlrev_b32_e32 v0, 3, v13
	v_ashrrev_i32_e32 v1, 31, v0
	v_mad_i64_i32 v[2:3], s[10:11], v12, s24, v[8:9]
	v_lshl_add_u64 v[0:1], v[0:1], 1, v[2:3]
	s_waitcnt lgkmcnt(0)
	global_store_dwordx4 v[0:1], v[4:7], off
	s_cbranch_scc0 .LBB0_110

; __device__ void phase_inproj(const Params& p, int layer, char* smem) {
;     ...
;     if (cb >= 26 && cb <= 29) {
;       float mx = 0.f;
; #pragma unroll
;       for (int m = 0; m < 4; ++m)
; #pragma unroll
;         for (int j = 0; j < 4; ++j) {
;           float ss = 0.f;
; #pragma unroll
;           for (int n = 0; n < 4; ++n) ss += acc[m][n][j] * acc[m][n][j];
;           ss += __shfl_xor(ss, 1);
;           ss += __shfl_xor(ss, 2);
;           ss += __shfl_xor(ss, 4);
;           ss += __shfl_xor(ss, 8);
;           mx = fmaxf(mx, ss);
;         }
.LBB0_107:
	s_sub_i32 s6, s12, 26
	s_cmp_gt_u32 s6, 3
	s_cbranch_scc1 .LBB0_102
	v_and_b32_e32 v65, 64, v129
	v_xor_b32_e32 v64, 1, v129
	v_add_u32_e32 v65, 64, v65
	v_mul_f32_e32 v66, v44, v44
	v_mul_f32_e32 v71, v45, v45
	v_cmp_lt_i32_e32 vcc, v64, v65
	v_fmac_f32_e32 v66, v40, v40
	v_fmac_f32_e32 v71, v41, v41
	v_mul_f32_e32 v73, v46, v46
	v_mul_f32_e32 v75, v47, v47
	v_cndmask_b32_e32 v64, v129, v64, vcc
	v_fmac_f32_e32 v66, v36, v36
	v_fmac_f32_e32 v71, v37, v37
	v_fmac_f32_e32 v73, v42, v42
	v_fmac_f32_e32 v75, v43, v43
	v_lshlrev_b32_e32 v64, 2, v64
	v_fmac_f32_e32 v66, v32, v32
	v_fmac_f32_e32 v71, v33, v33
	v_fmac_f32_e32 v73, v38, v38
	v_fmac_f32_e32 v75, v39, v39
	ds_bpermute_b32 v67, v64, v66
	ds_bpermute_b32 v72, v64, v71
	v_fmac_f32_e32 v73, v34, v34
	v_fmac_f32_e32 v75, v35, v35
	ds_bpermute_b32 v74, v64, v73
	ds_bpermute_b32 v76, v64, v75
	v_xor_b32_e32 v68, 2, v129
	v_cmp_lt_i32_e32 vcc, v68, v65
	s_waitcnt lgkmcnt(3)
	v_add_f32_e32 v66, v66, v67
	s_waitcnt lgkmcnt(2)
	v_add_f32_e32 v71, v71, v72
	v_cndmask_b32_e32 v68, v129, v68, vcc
	v_lshlrev_b32_e32 v68, 2, v68
	ds_bpermute_b32 v67, v68, v66
	ds_bpermute_b32 v72, v68, v71
	s_waitcnt lgkmcnt(3)
	v_add_f32_e32 v73, v73, v74
	s_waitcnt lgkmcnt(2)
	v_add_f32_e32 v75, v75, v76
	ds_bpermute_b32 v74, v68, v73
	ds_bpermute_b32 v76, v68, v75
	v_xor_b32_e32 v69, 4, v129
	v_cmp_lt_i32_e32 vcc, v69, v65
	s_waitcnt lgkmcnt(3)
	v_add_f32_e32 v66, v66, v67
	s_waitcnt lgkmcnt(2)
	v_add_f32_e32 v71, v71, v72
	v_cndmask_b32_e32 v69, v129, v69, vcc
	v_lshlrev_b32_e32 v69, 2, v69
	ds_bpermute_b32 v67, v69, v66
	ds_bpermute_b32 v72, v69, v71
	s_waitcnt lgkmcnt(3)
	v_add_f32_e32 v73, v73, v74
	s_waitcnt lgkmcnt(2)
	v_add_f32_e32 v75, v75, v76
	ds_bpermute_b32 v74, v69, v73
	ds_bpermute_b32 v76, v69, v75
	v_xor_b32_e32 v70, 8, v129
	v_cmp_lt_i32_e32 vcc, v70, v65
	s_waitcnt lgkmcnt(3)
	v_add_f32_e32 v66, v66, v67
	s_waitcnt lgkmcnt(2)
	v_add_f32_e32 v71, v71, v72
	v_cndmask_b32_e32 v70, v129, v70, vcc
	v_lshlrev_b32_e32 v70, 2, v70
	ds_bpermute_b32 v67, v70, v66
	ds_bpermute_b32 v72, v70, v71
	s_waitcnt lgkmcnt(3)
	v_add_f32_e32 v73, v73, v74
	s_waitcnt lgkmcnt(2)
	v_add_f32_e32 v75, v75, v76
	ds_bpermute_b32 v74, v70, v73
	ds_bpermute_b32 v76, v70, v75
	s_waitcnt lgkmcnt(3)
	v_add_f32_e32 v66, v66, v67
	s_waitcnt lgkmcnt(2)
	v_add_f32_e32 v67, v71, v72
	v_max3_f32 v66, v66, 0, v67
	s_waitcnt lgkmcnt(1)
	v_add_f32_e32 v67, v73, v74
	s_waitcnt lgkmcnt(0)
	v_add_f32_e32 v71, v75, v76
	v_max3_f32 v66, v66, v67, v71
	v_mul_f32_e32 v67, v28, v28
	v_mul_f32_e32 v72, v29, v29
	v_fmac_f32_e32 v67, v24, v24
	v_fmac_f32_e32 v72, v25, v25
	v_mul_f32_e32 v74, v30, v30
	v_fmac_f32_e32 v67, v20, v20
	v_fmac_f32_e32 v72, v21, v21
	v_fmac_f32_e32 v74, v26, v26
	v_fmac_f32_e32 v67, v16, v16
	v_fmac_f32_e32 v72, v17, v17
	v_fmac_f32_e32 v74, v22, v22
	ds_bpermute_b32 v71, v64, v67
	ds_bpermute_b32 v73, v64, v72
	v_fmac_f32_e32 v74, v18, v18
	ds_bpermute_b32 v75, v64, v74
	v_mul_f32_e32 v76, v31, v31
	s_waitcnt lgkmcnt(2)
	v_add_f32_e32 v67, v67, v71
	s_waitcnt lgkmcnt(1)
	v_add_f32_e32 v72, v72, v73
	ds_bpermute_b32 v71, v68, v67
	ds_bpermute_b32 v73, v68, v72
	s_waitcnt lgkmcnt(2)
	v_add_f32_e32 v74, v74, v75
	ds_bpermute_b32 v75, v68, v74
	v_fmac_f32_e32 v76, v27, v27
	s_waitcnt lgkmcnt(2)
	v_add_f32_e32 v67, v67, v71
	s_waitcnt lgkmcnt(1)
	v_add_f32_e32 v72, v72, v73
	ds_bpermute_b32 v71, v69, v67
	ds_bpermute_b32 v73, v69, v72
	s_waitcnt lgkmcnt(2)
	v_add_f32_e32 v74, v74, v75
	ds_bpermute_b32 v75, v69, v74
	v_fmac_f32_e32 v76, v23, v23
	s_waitcnt lgkmcnt(2)
	v_add_f32_e32 v67, v67, v71
	s_waitcnt lgkmcnt(1)
	v_add_f32_e32 v72, v72, v73
	ds_bpermute_b32 v71, v70, v67
	ds_bpermute_b32 v73, v70, v72
	s_waitcnt lgkmcnt(2)
	v_add_f32_e32 v74, v74, v75
	ds_bpermute_b32 v75, v70, v74
	v_fmac_f32_e32 v76, v19, v19
	ds_bpermute_b32 v77, v64, v76
	s_waitcnt lgkmcnt(3)
	v_add_f32_e32 v67, v67, v71
	s_waitcnt lgkmcnt(2)
	v_add_f32_e32 v71, v72, v73
	v_max3_f32 v66, v66, v67, v71
	s_waitcnt lgkmcnt(1)
	v_add_f32_e32 v67, v74, v75
	v_mul_f32_e32 v73, v12, v12
	v_mul_f32_e32 v75, v13, v13
	v_fmac_f32_e32 v73, v8, v8
	v_fmac_f32_e32 v75, v9, v9
	s_waitcnt lgkmcnt(0)
	v_add_f32_e32 v71, v76, v77
	v_fmac_f32_e32 v73, v4, v4
	v_fmac_f32_e32 v75, v5, v5
	ds_bpermute_b32 v72, v68, v71
	v_fmac_f32_e32 v73, v0, v0
	v_fmac_f32_e32 v75, v1, v1
	ds_bpermute_b32 v74, v64, v73
	ds_bpermute_b32 v76, v64, v75
	s_waitcnt lgkmcnt(2)
	v_add_f32_e32 v71, v71, v72
	ds_bpermute_b32 v72, v69, v71
	s_waitcnt lgkmcnt(2)
	v_add_f32_e32 v73, v73, v74
	s_waitcnt lgkmcnt(1)
; __device__ void phase_inproj(const Params& p, int layer, char* smem) {
;     ...
;       float mx = 0.f;
; #pragma unroll
;       for (int m = 0; m < 4; ++m)
; #pragma unroll
;         for (int j = 0; j < 4; ++j) {
;           float ss = 0.f;
; #pragma unroll
;           for (int n = 0; n < 4; ++n) ss += acc[m][n][j] * acc[m][n][j];
;           ss += __shfl_xor(ss, 1);
;           ss += __shfl_xor(ss, 2);
;           ss += __shfl_xor(ss, 4);
;           ss += __shfl_xor(ss, 8);
;           mx = fmaxf(mx, ss);
;         }
;       mx = fmaxf(mx, __shfl_xor(mx, 16));
;       mx = fmaxf(mx, __shfl_xor(mx, 32));
;       if (lane == 0) {
;         unsigned* km = reinterpret_cast<unsigned*>(wsb(p) + OFF_MISC) + 64 + layer * 16 + (rb >> 7) * 8 + (cb - 26) * 2 + wc;
;         atomicMax(km, __float_as_uint(mx));
;       }
	v_add_f32_e32 v75, v75, v76
	ds_bpermute_b32 v74, v68, v73
	ds_bpermute_b32 v76, v68, v75
	s_waitcnt lgkmcnt(2)
	v_add_f32_e32 v71, v71, v72
	ds_bpermute_b32 v72, v70, v71
	s_waitcnt lgkmcnt(2)
	v_add_f32_e32 v73, v73, v74
	s_waitcnt lgkmcnt(1)
	v_add_f32_e32 v75, v75, v76
	ds_bpermute_b32 v74, v69, v73
	ds_bpermute_b32 v76, v69, v75
	s_waitcnt lgkmcnt(2)
	v_add_f32_e32 v71, v71, v72
	v_max3_f32 v66, v66, v67, v71
	s_waitcnt lgkmcnt(1)
	v_add_f32_e32 v67, v73, v74
	s_waitcnt lgkmcnt(0)
	v_add_f32_e32 v72, v75, v76
	v_mul_f32_e32 v74, v14, v14
	v_mul_f32_e32 v76, v15, v15
	v_fmac_f32_e32 v74, v10, v10
	v_fmac_f32_e32 v76, v11, v11
	v_fmac_f32_e32 v74, v6, v6
	v_fmac_f32_e32 v76, v7, v7
	v_fmac_f32_e32 v74, v2, v2
	v_fmac_f32_e32 v76, v3, v3
	ds_bpermute_b32 v71, v70, v67
	ds_bpermute_b32 v73, v70, v72
	ds_bpermute_b32 v75, v64, v74
	ds_bpermute_b32 v77, v64, v76
	s_waitcnt lgkmcnt(3)
	v_add_f32_e32 v67, v67, v71
	s_waitcnt lgkmcnt(2)
	v_add_f32_e32 v71, v72, v73
	s_waitcnt lgkmcnt(1)
	v_add_f32_e32 v72, v74, v75
	s_waitcnt lgkmcnt(0)
	v_add_f32_e32 v74, v76, v77
	v_mul_f32_e32 v76, v60, v60
	v_fmac_f32_e32 v76, v56, v56
	v_fmac_f32_e32 v76, v52, v52
	ds_bpermute_b32 v73, v68, v72
	ds_bpermute_b32 v75, v68, v74
	v_fmac_f32_e32 v76, v48, v48
	ds_bpermute_b32 v77, v64, v76
	v_max3_f32 v66, v66, v67, v71
	s_waitcnt lgkmcnt(2)
	v_add_f32_e32 v72, v72, v73
	s_waitcnt lgkmcnt(1)
	v_add_f32_e32 v74, v74, v75
	ds_bpermute_b32 v73, v69, v72
	ds_bpermute_b32 v75, v69, v74
	s_waitcnt lgkmcnt(2)
	v_add_f32_e32 v76, v76, v77
	ds_bpermute_b32 v77, v68, v76
	s_waitcnt lgkmcnt(2)
	v_add_f32_e32 v72, v72, v73
	s_waitcnt lgkmcnt(1)
	v_add_f32_e32 v74, v74, v75
	ds_bpermute_b32 v73, v70, v72
	ds_bpermute_b32 v75, v70, v74
	s_waitcnt lgkmcnt(2)
	v_add_f32_e32 v76, v76, v77
	ds_bpermute_b32 v77, v69, v76
	s_waitcnt lgkmcnt(2)
	v_add_f32_e32 v67, v72, v73
	s_waitcnt lgkmcnt(1)
	v_add_f32_e32 v71, v74, v75
	v_mul_f32_e32 v72, v61, v61
	v_max3_f32 v66, v66, v67, v71
	s_waitcnt lgkmcnt(0)
	v_add_f32_e32 v67, v76, v77
	v_fmac_f32_e32 v72, v57, v57
	v_mul_f32_e32 v74, v62, v62
	v_mul_f32_e32 v76, v63, v63
	v_fmac_f32_e32 v72, v53, v53
	v_fmac_f32_e32 v74, v58, v58
	v_fmac_f32_e32 v76, v59, v59
	v_fmac_f32_e32 v72, v49, v49
	v_fmac_f32_e32 v74, v54, v54
	v_fmac_f32_e32 v76, v55, v55
	ds_bpermute_b32 v73, v64, v72
	v_fmac_f32_e32 v74, v50, v50
	v_fmac_f32_e32 v76, v51, v51
	ds_bpermute_b32 v75, v64, v74
	ds_bpermute_b32 v64, v64, v76
	s_waitcnt lgkmcnt(2)
	v_add_f32_e32 v72, v72, v73
	ds_bpermute_b32 v73, v68, v72
	ds_bpermute_b32 v71, v70, v67
	s_waitcnt lgkmcnt(3)
	v_add_f32_e32 v74, v74, v75
	s_waitcnt lgkmcnt(2)
	v_add_f32_e32 v64, v76, v64
	ds_bpermute_b32 v75, v68, v74
	ds_bpermute_b32 v68, v68, v64
	s_waitcnt lgkmcnt(3)
	v_add_f32_e32 v72, v72, v73
	ds_bpermute_b32 v73, v69, v72
	s_waitcnt lgkmcnt(3)
	v_add_f32_e32 v67, v67, v71
	s_waitcnt lgkmcnt(2)
	v_add_f32_e32 v74, v74, v75
	s_waitcnt lgkmcnt(1)
	v_add_f32_e32 v64, v64, v68
	ds_bpermute_b32 v75, v69, v74
	ds_bpermute_b32 v68, v69, v64
	s_waitcnt lgkmcnt(2)
	v_add_f32_e32 v69, v72, v73
	ds_bpermute_b32 v72, v70, v69
	s_waitcnt lgkmcnt(2)
	v_add_f32_e32 v73, v74, v75
	s_waitcnt lgkmcnt(1)
	v_add_f32_e32 v64, v64, v68
	ds_bpermute_b32 v74, v70, v73
	ds_bpermute_b32 v68, v70, v64
	s_waitcnt lgkmcnt(2)
	v_add_f32_e32 v69, v69, v72
	v_max3_f32 v66, v66, v67, v69
	s_waitcnt lgkmcnt(1)
	v_add_f32_e32 v67, v73, v74
	s_waitcnt lgkmcnt(0)
	v_add_f32_e32 v64, v64, v68
	v_max3_f32 v64, v66, v67, v64
	v_xor_b32_e32 v66, 16, v129
	v_cmp_lt_i32_e32 vcc, v66, v65
	s_nop 1
	v_cndmask_b32_e32 v66, v129, v66, vcc
	v_lshlrev_b32_e32 v66, 2, v66
	ds_bpermute_b32 v66, v66, v64
	s_waitcnt lgkmcnt(0)
	v_max_f32_e32 v64, v64, v66
	v_xor_b32_e32 v66, 32, v129
	v_cmp_lt_i32_e32 vcc, v66, v65
	s_nop 1
	v_cndmask_b32_e32 v65, v129, v66, vcc
	v_lshlrev_b32_e32 v65, 2, v65
	ds_bpermute_b32 v65, v65, v64
	s_and_saveexec_b64 s[14:15], s[4:5]
	s_cbranch_execz .LBB0_101
	s_waitcnt lgkmcnt(0)
	v_max_f32_e32 v66, v64, v65
	v_mov_b32_e32 v64, v117
	v_mov_b32_e32 v119, v117
	v_readfirstlane_b32 s6, v64
	s_ashr_i32 s11, s6, 31
	s_add_u32 s6, s28, s6
	s_addc_u32 s11, s29, s11
	s_ashr_i32 s13, s10, 4
	s_and_b32 s20, s13, -8
	s_ashr_i32 s21, s20, 31
	s_lshl_b64 s[20:21], s[20:21], 2
	s_add_u32 s13, s6, s20
	s_addc_u32 s11, s11, s21
	s_lshl_b32 s6, s12, 1
	s_lshl_b64 s[20:21], s[6:7], 2
	s_add_u32 s20, s13, s20
	s_addc_u32 s21, s11, s21
	v_lshl_add_u64 v[64:65], s[20:21], 0, v[118:119]
	v_add_co_u32_e32 v64, vcc, 0x1e8a4000, v64
	s_nop 1
	v_addc_co_u32_e32 v65, vcc, 0, v65, vcc
	global_atomic_umax v[64:65], v66, off offset:2096
	s_branch .LBB0_101

; template <int DH, int MODE>
; __device__ void attn_item(const Params& p, int layer, int b, int blk, int head, char* smem) {
;     ...
;     uint4 gt[NCH];
; #pragma unroll
;     for (int i = 0; i < NCH; ++i) {
;       int q = tid + 256 * i, r = q / CPR, c = (q % CPR) * 8;
;       gt[i] = *reinterpret_cast<const uint4*>(P + (tq0 + r) * NP + gcol + c);
;     }
;     float lis[2][4];
; #pragma unroll
;     for (int m = 0; m < 2; ++m)
; #pragma unroll
;       for (int j = 0; j < 4; ++j) lis[m][j] = (MODE == 0) ? linv_s[wid * 32 + m * 16 + fq * 4 + j] : 1.f;
;     if (MODE == 0) __syncthreads();
; #pragma unroll
;     for (int m = 0; m < 2; ++m)
; #pragma unroll
;       for (int j = 0; j < 4; ++j) {
;         int r = wid * 32 + m * 16 + fq * 4 + j;
; #pragma unroll
;         for (int n = 0; n < NDT; ++n) Of[r * OST + n * 16 + fr] = o[m][n][j] * lis[m][j];
;       }
;     __syncthreads();
.LBB0_149:
	s_ashr_i32 s5, s83, 31
	s_add_u32 s4, s28, s83
	s_addc_u32 s5, s29, s5
	s_lshl_b32 s6, s80, 1
	s_add_u32 s8, s48, s6
	s_addc_u32 s9, s49, 0
	v_lshl_add_u64 v[2:3], s[10:11], 0, v[134:135]
	v_mov_b64_e32 v[4:5], s[8:9]
	v_mad_u64_u32 v[0:1], s[8:9], v2, s55, v[4:5]
	v_mad_i32_i24 v1, v3, s55, v1
	s_waitcnt vmcnt(12)
	v_lshl_add_u64 v[76:77], v[0:1], 0, v[138:139]
	v_add_u32_e32 v0, 0x100, v161
	v_ashrrev_i32_e32 v1, 31, v0
	v_lshrrev_b32_e32 v1, 28, v1
	v_add_u32_e32 v1, v0, v1
	v_ashrrev_i32_e32 v8, 4, v1
	v_and_b32_e32 v1, -16, v1
	s_waitcnt vmcnt(5)
	v_sub_u32_e32 v99, v0, v1
	v_lshlrev_b32_e32 v0, 3, v99
	v_ashrrev_i32_e32 v1, 31, v0
	s_waitcnt vmcnt(3)
	v_lshlrev_b64 v[92:93], 1, v[0:1]
	v_add_u32_e32 v0, 0x200, v161
	v_ashrrev_i32_e32 v1, 31, v0
	v_lshrrev_b32_e32 v1, 28, v1
	v_add_u32_e32 v1, v0, v1
	v_ashrrev_i32_e32 v9, 31, v8
	v_ashrrev_i32_e32 v94, 4, v1
	v_and_b32_e32 v1, -16, v1
	v_lshl_add_u64 v[10:11], s[10:11], 0, v[8:9]
	v_sub_u32_e32 v9, v0, v1
	v_lshlrev_b32_e32 v0, 3, v9
	v_ashrrev_i32_e32 v1, 31, v0
	v_lshlrev_b64 v[100:101], 1, v[0:1]
	v_add_u32_e32 v0, 0x300, v161
	v_ashrrev_i32_e32 v1, 31, v0
	v_lshrrev_b32_e32 v1, 28, v1
	v_add_u32_e32 v1, v0, v1
	v_ashrrev_i32_e32 v102, 4, v1
	v_and_b32_e32 v1, -16, v1
	v_sub_u32_e32 v128, v0, v1
	v_lshlrev_b32_e32 v0, 3, v128
	v_ashrrev_i32_e32 v1, 31, v0
	s_waitcnt vmcnt(0)
	v_lshlrev_b64 v[106:107], 1, v[0:1]
	v_add_u32_e32 v0, 0x400, v161
	v_ashrrev_i32_e32 v1, 31, v0
	v_lshrrev_b32_e32 v1, 28, v1
	v_add_u32_e32 v1, v0, v1
	v_ashrrev_i32_e32 v103, 31, v102
	v_ashrrev_i32_e32 v108, 4, v1
	v_and_b32_e32 v1, -16, v1
	v_lshl_add_u64 v[104:105], s[10:11], 0, v[102:103]
	v_sub_u32_e32 v103, v0, v1
	v_lshlrev_b32_e32 v0, 3, v103
	v_ashrrev_i32_e32 v1, 31, v0
	v_lshlrev_b64 v[112:113], 1, v[0:1]
	v_add_u32_e32 v0, 0x500, v161
	v_ashrrev_i32_e32 v1, 31, v0
	v_lshrrev_b32_e32 v1, 28, v1
	v_add_u32_e32 v1, v0, v1
	v_ashrrev_i32_e32 v109, 31, v108
	v_ashrrev_i32_e32 v114, 4, v1
	v_and_b32_e32 v1, -16, v1
	v_mad_u64_u32 v[6:7], s[8:9], v10, s55, v[4:5]
	v_ashrrev_i32_e32 v95, 31, v94
	v_lshl_add_u64 v[110:111], s[10:11], 0, v[108:109]
	v_sub_u32_e32 v109, v0, v1
	v_mad_i32_i24 v7, v11, s55, v7
	v_lshl_add_u64 v[96:97], s[10:11], 0, v[94:95]
	v_lshlrev_b32_e32 v0, 3, v109
	v_lshl_add_u64 v[78:79], v[6:7], 0, v[92:93]
	v_mad_u64_u32 v[6:7], s[8:9], v96, s55, v[4:5]
	v_ashrrev_i32_e32 v1, 31, v0
	v_mad_i32_i24 v7, v97, s55, v7
	v_lshlrev_b64 v[118:119], 1, v[0:1]
	v_add_u32_e32 v0, 0x600, v161
	v_lshl_add_u64 v[80:81], v[6:7], 0, v[100:101]
	v_mad_u64_u32 v[6:7], s[8:9], v104, s55, v[4:5]
	v_ashrrev_i32_e32 v1, 31, v0
	v_mad_i32_i24 v7, v105, s55, v7
	v_lshrrev_b32_e32 v1, 28, v1
	v_lshl_add_u64 v[82:83], v[6:7], 0, v[106:107]
	v_mad_u64_u32 v[6:7], s[8:9], v110, s55, v[4:5]
	v_ashrrev_i32_e32 v115, 31, v114
	v_add_u32_e32 v1, v0, v1
	v_mad_i32_i24 v7, v111, s55, v7
	v_lshl_add_u64 v[116:117], s[10:11], 0, v[114:115]
	v_ashrrev_i32_e32 v120, 4, v1
	v_and_b32_e32 v1, -16, v1
	v_lshl_add_u64 v[84:85], v[6:7], 0, v[112:113]
	v_mad_u64_u32 v[6:7], s[8:9], v116, s55, v[4:5]
	v_sub_u32_e32 v115, v0, v1
	v_ashrrev_i32_e32 v121, 31, v120
	v_mad_i32_i24 v7, v117, s55, v7
	v_lshlrev_b32_e32 v0, 3, v115
	v_lshl_add_u64 v[122:123], s[10:11], 0, v[120:121]
	v_lshl_add_u64 v[86:87], v[6:7], 0, v[118:119]
	v_mad_u64_u32 v[6:7], s[8:9], v122, s55, v[4:5]
	v_ashrrev_i32_e32 v1, 31, v0
	v_mad_i32_i24 v7, v123, s55, v7
	v_lshlrev_b64 v[124:125], 1, v[0:1]
	v_lshl_add_u64 v[0:1], v[6:7], 0, v[124:125]
	v_add_u32_e32 v6, 0x700, v161
	v_ashrrev_i32_e32 v7, 31, v6
	v_lshrrev_b32_e32 v7, 28, v7
	v_add_u32_e32 v7, v6, v7
	v_ashrrev_i32_e32 v126, 4, v7
	v_and_b32_e32 v7, -16, v7
	v_sub_u32_e32 v121, v6, v7
	v_lshlrev_b32_e32 v6, 3, v121
	v_ashrrev_i32_e32 v127, 31, v126
	v_lshl_add_u64 v[88:89], s[10:11], 0, v[126:127]
	v_ashrrev_i32_e32 v7, 31, v6
	v_mad_u64_u32 v[4:5], s[8:9], v88, s55, v[4:5]
	v_lshlrev_b64 v[90:91], 1, v[6:7]
	v_lshl_or_b32 v6, v137, 2, v130
	v_mad_i32_i24 v5, v89, s55, v5
	v_mul_lo_u32 v6, v6, s67
	v_lshl_add_u64 v[4:5], v[4:5], 0, v[90:91]
	v_lshl_add_u32 v95, v162, 2, v6
	s_barrier
	ds_write2_b32 v95, v12, v48 offset1:16
	ds_write2_b32 v95, v52, v56 offset0:32 offset1:48
	ds_write2_b32 v95, v60, v64 offset0:64 offset1:80
	ds_write2_b32 v95, v68, v72 offset0:96 offset1:112
	ds_write2_b32 v95, v13, v49 offset0:132 offset1:148
	ds_write2_b32 v95, v53, v57 offset0:164 offset1:180
	ds_write2_b32 v95, v61, v65 offset0:196 offset1:212
	ds_write2_b32 v95, v69, v73 offset0:228 offset1:244
	v_add_u32_e32 v12, 0x400, v95
	v_add_co_u32_e32 v4, vcc, s77, v4
	ds_write2_b32 v12, v14, v50 offset0:8 offset1:24
	ds_write2_b32 v12, v54, v58 offset0:40 offset1:56
	v_addc_co_u32_e32 v5, vcc, 0, v5, vcc
	global_load_dwordx4 v[4:7], v[4:5], off offset:512
	ds_write2_b32 v12, v62, v66 offset0:72 offset1:88
	ds_write2_b32 v12, v70, v74 offset0:104 offset1:120
	ds_write2_b32 v12, v15, v51 offset0:140 offset1:156
	ds_write2_b32 v12, v55, v59 offset0:172 offset1:188
	ds_write2_b32 v12, v63, v67 offset0:204 offset1:220
	ds_write2_b32 v12, v71, v75 offset0:236 offset1:252
	v_add_u32_e32 v12, 0x2000, v95
	ds_write2_b32 v12, v16, v20 offset0:64 offset1:80
	ds_write2_b32 v12, v24, v36 offset0:96 offset1:112
	ds_write2_b32 v12, v28, v40 offset0:128 offset1:144
	ds_write2_b32 v12, v44, v32 offset0:160 offset1:176
	ds_write2_b32 v12, v17, v21 offset0:196 offset1:212
	ds_write2_b32 v12, v25, v37 offset0:228 offset1:244
	v_add_u32_e32 v12, 0x2400, v95
	s_add_u32 s4, s4, s6
	ds_write2_b32 v12, v29, v41 offset0:4 offset1:20
	ds_write2_b32 v12, v45, v33 offset0:36 offset1:52
	ds_write2_b32 v12, v18, v22 offset0:72 offset1:88
; __device__ __forceinline__ unsigned pack2(float a, float b) { return (unsigned)f2bf(a) | ((unsigned)f2bf(b) << 16); }
; __device__ __forceinline__ float bflo(unsigned w) { return __uint_as_float(w << 16); }
; __device__ __forceinline__ float bfhi(unsigned w) { return __uint_as_float(w & 0xffff0000u); }
; __device__ __forceinline__ float silu_f(float g) { return g / (1.f + __expf(-g)); }
; template <int DH, int MODE>
; __device__ void attn_item(const Params& p, int layer, int b, int blk, int head, char* smem) {
;     ...
; #pragma unroll
;     for (int m = 0; m < 2; ++m)
; #pragma unroll
;       for (int j = 0; j < 4; ++j) {
;         int r = wid * 32 + m * 16 + fq * 4 + j;
; #pragma unroll
;         for (int n = 0; n < NDT; ++n) Of[r * OST + n * 16 + fr] = o[m][n][j] * lis[m][j];
;       }
;     __syncthreads();
; #pragma unroll
;     for (int i = 0; i < NCH; ++i) {
;       int q = tid + 256 * i, r = q / CPR, c = (q % CPR) * 8;
;       float4 m0 = *reinterpret_cast<const float4*>(Of + r * OST + c);
;       float4 m1 = *reinterpret_cast<const float4*>(Of + r * OST + c + 4);
;       float mm[8] = {m0.x, m0.y, m0.z, m0.w, m1.x, m1.y, m1.z, m1.w};
;       unsigned gw[4] = {gt[i].x, gt[i].y, gt[i].z, gt[i].w};
;       unsigned ow[4];
; #pragma unroll
;       for (int e = 0; e < 4; ++e)
;         ow[e] = pack2(mm[2 * e] * silu_f(bflo(gw[e])), mm[2 * e + 1] * silu_f(bfhi(gw[e])));
	ds_write2_b32 v12, v26, v38 offset0:104 offset1:120
	ds_write2_b32 v12, v30, v42 offset0:136 offset1:152
	ds_write2_b32 v12, v46, v34 offset0:168 offset1:184
	ds_write2_b32 v12, v19, v23 offset0:204 offset1:220
	ds_write2_b32 v12, v27, v39 offset0:236 offset1:252
	v_add_u32_e32 v12, 0x2800, v95
	s_addc_u32 s5, s5, 0
	ds_write2_b32 v12, v31, v43 offset0:12 offset1:28
	ds_write2_b32 v12, v47, v35 offset0:44 offset1:60
	v_mul_lo_u32 v12, v134, s67
	v_mov_b64_e32 v[14:15], s[4:5]
	v_lshl_add_u32 v98, v136, 2, v12
	v_mad_u64_u32 v[12:13], s[4:5], v2, s68, v[14:15]
	v_mul_lo_u32 v2, v8, s67
	v_mad_i32_i24 v13, v3, s68, v13
	v_lshl_add_u32 v95, v99, 5, v2
	v_mad_u64_u32 v[2:3], s[4:5], v10, s68, v[14:15]
	v_mad_i32_i24 v3, v11, s68, v3
	v_lshl_add_u64 v[26:27], v[2:3], 0, v[92:93]
	v_mul_lo_u32 v2, v94, s67
	v_lshl_add_u32 v93, v9, 5, v2
	v_mad_u64_u32 v[2:3], s[4:5], v96, s68, v[14:15]
	v_mad_i32_i24 v3, v97, s68, v3
	v_lshl_add_u64 v[20:21], v[2:3], 0, v[100:101]
	v_mul_lo_u32 v2, v102, s67
	v_lshl_add_u32 v92, v128, 5, v2
	v_mad_u64_u32 v[2:3], s[4:5], v104, s68, v[14:15]
	v_mad_i32_i24 v3, v105, s68, v3
	v_lshl_add_u64 v[16:17], v[2:3], 0, v[106:107]
	v_mul_lo_u32 v2, v108, s67
	v_lshl_add_u32 v75, v103, 5, v2
	v_mad_u64_u32 v[2:3], s[4:5], v110, s68, v[14:15]
	v_mad_i32_i24 v3, v111, s68, v3
	v_lshl_add_u64 v[30:31], v[12:13], 0, v[138:139]
	v_lshl_add_u64 v[12:13], v[2:3], 0, v[112:113]
	v_mul_lo_u32 v2, v114, s67
	v_lshl_add_u32 v74, v109, 5, v2
	v_mad_u64_u32 v[2:3], s[4:5], v116, s68, v[14:15]
	v_mad_i32_i24 v3, v117, s68, v3
	v_lshl_add_u64 v[10:11], v[2:3], 0, v[118:119]
	v_mul_lo_u32 v2, v120, s67
	v_lshl_add_u32 v73, v115, 5, v2
	v_mad_u64_u32 v[2:3], s[4:5], v122, s68, v[14:15]
	v_mad_i32_i24 v3, v123, s68, v3
	v_add_co_u32_e32 v0, vcc, s77, v0
	v_lshl_add_u64 v[8:9], v[2:3], 0, v[124:125]
	v_mul_lo_u32 v2, v126, s67
	v_addc_co_u32_e32 v1, vcc, 0, v1, vcc
	v_lshl_add_u32 v72, v121, 5, v2
	global_load_dwordx4 v[0:3], v[0:1], off offset:512
	v_mad_u64_u32 v[14:15], s[4:5], v88, s68, v[14:15]
	v_mad_i32_i24 v15, v89, s68, v15
	v_lshl_add_u64 v[14:15], v[14:15], 0, v[90:91]
	s_waitcnt vmcnt(1)
	v_lshlrev_b32_e32 v22, 16, v5
	v_lshlrev_b32_e32 v23, 16, v4
	v_mul_f32_e32 v18, 0xbfb8aa3b, v23
	v_mul_f32_e32 v19, 0xbfb8aa3b, v22
	v_exp_f32_e32 v18, v18
	v_exp_f32_e32 v19, v19
	v_and_b32_e32 v24, 0xffff0000, v5
	v_and_b32_e32 v28, 0xffff0000, v4
	v_mul_f32_e32 v4, 0xbfb8aa3b, v28
	v_pk_add_f32 v[18:19], v[18:19], 1.0 op_sel_hi:[1,0]
	v_exp_f32_e32 v4, v4
	v_and_b32_e32 v34, 0xffff0000, v6
	v_rcp_f32_e32 v19, v19
	s_nop 0
	v_mul_f32_e32 v19, v22, v19
	v_mul_f32_e32 v5, 0xbfb8aa3b, v24
	v_exp_f32_e32 v5, v5
	s_nop 0
	v_pk_add_f32 v[4:5], v[4:5], 1.0 op_sel_hi:[1,0]
	v_rcp_f32_e32 v18, v18
	s_nop 0
	v_mul_f32_e32 v18, v23, v18
	v_lshlrev_b32_e32 v33, 16, v6
	v_rcp_f32_e32 v23, v5
	s_nop 0
	v_mul_f32_e32 v23, v24, v23
	v_lshlrev_b32_e32 v32, 16, v7
	v_mul_f32_e32 v24, 0xbfb8aa3b, v33
	v_mul_f32_e32 v25, 0xbfb8aa3b, v32
	v_exp_f32_e32 v24, v24
	v_exp_f32_e32 v25, v25
	v_rcp_f32_e32 v22, v4
	s_nop 0
	v_mul_f32_e32 v22, v28, v22
	v_and_b32_e32 v28, 0xffff0000, v7
	v_pk_add_f32 v[4:5], v[24:25], 1.0 op_sel_hi:[1,0]
	v_mul_f32_e32 v6, 0xbfb8aa3b, v34
	v_exp_f32_e32 v6, v6
	s_waitcnt vmcnt(0)
	v_lshlrev_b32_e32 v40, 16, v3
	v_lshlrev_b32_e32 v41, 16, v2
	v_rcp_f32_e32 v25, v5
	s_nop 0
	v_mul_f32_e32 v25, v32, v25
	v_mul_f32_e32 v7, 0xbfb8aa3b, v28
	v_exp_f32_e32 v7, v7
	s_nop 0
	v_pk_add_f32 v[6:7], v[6:7], 1.0 op_sel_hi:[1,0]
	v_rcp_f32_e32 v24, v4
	s_nop 0
	v_mul_f32_e32 v24, v33, v24
	v_rcp_f32_e32 v29, v7
	s_nop 0
	v_mul_f32_e32 v29, v28, v29
	v_lshlrev_b32_e32 v32, 16, v1
	v_lshlrev_b32_e32 v36, 16, v0
	v_mul_f32_e32 v4, 0xbfb8aa3b, v36
	v_mul_f32_e32 v5, 0xbfb8aa3b, v32
	v_exp_f32_e32 v4, v4
	v_exp_f32_e32 v5, v5
	v_rcp_f32_e32 v28, v6
	s_nop 0
	v_mul_f32_e32 v28, v34, v28
	v_and_b32_e32 v6, 0xffff0000, v1
	v_pk_add_f32 v[4:5], v[4:5], 1.0 op_sel_hi:[1,0]
	v_and_b32_e32 v34, 0xffff0000, v0
	v_mul_f32_e32 v0, 0xbfb8aa3b, v34
	v_exp_f32_e32 v0, v0
	v_and_b32_e32 v42, 0xffff0000, v3
	v_rcp_f32_e32 v33, v5
	s_nop 0
	v_mul_f32_e32 v33, v32, v33
	v_mul_f32_e32 v1, 0xbfb8aa3b, v6
	v_exp_f32_e32 v1, v1
	s_nop 0
	v_pk_add_f32 v[0:1], v[0:1], 1.0 op_sel_hi:[1,0]
	v_rcp_f32_e32 v32, v4
	s_nop 0
	v_mul_f32_e32 v32, v36, v32
	v_rcp_f32_e32 v35, v1
	s_nop 0
	v_mul_f32_e32 v35, v6, v35
	v_add_co_u32_e64 v4, s[4:5], s77, v86
	s_nop 0
	s_nop 0
	v_addc_co_u32_e64 v5, s[4:5], 0, v87, s[4:5]
	global_load_dwordx4 v[4:7], v[4:5], off offset:512
	v_mul_f32_e32 v36, 0xbfb8aa3b, v41
	v_mul_f32_e32 v37, 0xbfb8aa3b, v40
	v_exp_f32_e32 v36, v36
	v_exp_f32_e32 v37, v37
	v_rcp_f32_e32 v1, v0
	s_nop 0
	v_mul_f32_e32 v34, v34, v1
	v_and_b32_e32 v43, 0xffff0000, v2
	v_pk_add_f32 v[0:1], v[36:37], 1.0 op_sel_hi:[1,0]
	v_mul_f32_e32 v2, 0xbfb8aa3b, v43
	v_exp_f32_e32 v2, v2
	v_rcp_f32_e32 v37, v1
	s_nop 0
	v_mul_f32_e32 v37, v40, v37
	v_mul_f32_e32 v3, 0xbfb8aa3b, v42
	v_exp_f32_e32 v3, v3
	s_nop 0
	v_pk_add_f32 v[38:39], v[2:3], 1.0 op_sel_hi:[1,0]
	v_rcp_f32_e32 v36, v0
	s_nop 0
	v_mul_f32_e32 v36, v41, v36
	v_rcp_f32_e32 v39, v39
	s_nop 0
	v_mul_f32_e32 v39, v42, v39
	v_add_co_u32_e64 v0, s[4:5], s77, v84
	s_waitcnt vmcnt(0)
; __device__ __forceinline__ unsigned pack2(float a, float b) { return (unsigned)f2bf(a) | ((unsigned)f2bf(b) << 16); }
; __device__ __forceinline__ float bflo(unsigned w) { return __uint_as_float(w << 16); }
; __device__ __forceinline__ float bfhi(unsigned w) { return __uint_as_float(w & 0xffff0000u); }
; __device__ __forceinline__ float silu_f(float g) { return g / (1.f + __expf(-g)); }
; template <int DH, int MODE>
; __device__ void attn_item(const Params& p, int layer, int b, int blk, int head, char* smem) {
;     ...
;     __syncthreads();
; #pragma unroll
;     for (int i = 0; i < NCH; ++i) {
;       int q = tid + 256 * i, r = q / CPR, c = (q % CPR) * 8;
;       float4 m0 = *reinterpret_cast<const float4*>(Of + r * OST + c);
;       float4 m1 = *reinterpret_cast<const float4*>(Of + r * OST + c + 4);
;       float mm[8] = {m0.x, m0.y, m0.z, m0.w, m1.x, m1.y, m1.z, m1.w};
;       unsigned gw[4] = {gt[i].x, gt[i].y, gt[i].z, gt[i].w};
;       unsigned ow[4];
; #pragma unroll
;       for (int e = 0; e < 4; ++e)
;         ow[e] = pack2(mm[2 * e] * silu_f(bflo(gw[e])), mm[2 * e + 1] * silu_f(bfhi(gw[e])));
	v_lshlrev_b32_e32 v46, 16, v5
	v_lshlrev_b32_e32 v47, 16, v4
	v_mul_f32_e32 v40, 0xbfb8aa3b, v47
	v_mul_f32_e32 v41, 0xbfb8aa3b, v46
	v_exp_f32_e32 v40, v40
	v_exp_f32_e32 v41, v41
	v_addc_co_u32_e64 v1, s[4:5], 0, v85, s[4:5]
	v_rcp_f32_e32 v38, v38
	s_nop 0
	v_mul_f32_e32 v38, v43, v38
	v_pk_add_f32 v[40:41], v[40:41], 1.0 op_sel_hi:[1,0]
	v_and_b32_e32 v42, 0xffff0000, v5
	global_load_dwordx4 v[0:3], v[0:1], off offset:512
	v_and_b32_e32 v48, 0xffff0000, v4
	v_mul_f32_e32 v4, 0xbfb8aa3b, v48
	v_rcp_f32_e32 v41, v41
	s_nop 0
	v_mul_f32_e32 v41, v46, v41
	v_exp_f32_e32 v4, v4
	v_mul_f32_e32 v5, 0xbfb8aa3b, v42
	v_exp_f32_e32 v5, v5
	s_nop 0
	v_pk_add_f32 v[4:5], v[4:5], 1.0 op_sel_hi:[1,0]
	v_rcp_f32_e32 v40, v40
	s_nop 0
	v_mul_f32_e32 v40, v47, v40
	v_lshlrev_b32_e32 v49, 16, v6
	v_rcp_f32_e32 v43, v5
	s_nop 0
	v_mul_f32_e32 v43, v42, v43
	v_lshlrev_b32_e32 v46, 16, v7
	v_mul_f32_e32 v44, 0xbfb8aa3b, v49
	v_mul_f32_e32 v45, 0xbfb8aa3b, v46
	v_exp_f32_e32 v44, v44
	v_exp_f32_e32 v45, v45
	v_rcp_f32_e32 v42, v4
	s_nop 0
	v_mul_f32_e32 v42, v48, v42
	v_and_b32_e32 v47, 0xffff0000, v7
	v_pk_add_f32 v[4:5], v[44:45], 1.0 op_sel_hi:[1,0]
	v_and_b32_e32 v48, 0xffff0000, v6
	v_mul_f32_e32 v6, 0xbfb8aa3b, v48
	v_exp_f32_e32 v6, v6
	v_rcp_f32_e32 v45, v5
	s_nop 0
	v_mul_f32_e32 v45, v46, v45
	v_mul_f32_e32 v7, 0xbfb8aa3b, v47
	v_exp_f32_e32 v7, v7
	s_nop 0
	v_pk_add_f32 v[6:7], v[6:7], 1.0 op_sel_hi:[1,0]
	v_rcp_f32_e32 v44, v4
	s_nop 0
	v_mul_f32_e32 v44, v49, v44
	v_rcp_f32_e32 v4, v7
	s_nop 0
	v_mul_f32_e32 v47, v47, v4
	s_waitcnt vmcnt(0)
	v_lshlrev_b32_e32 v50, 16, v1
	v_lshlrev_b32_e32 v51, 16, v0
	v_mul_f32_e32 v4, 0xbfb8aa3b, v51
	v_mul_f32_e32 v5, 0xbfb8aa3b, v50
	v_exp_f32_e32 v4, v4
	v_exp_f32_e32 v5, v5
	v_rcp_f32_e32 v46, v6
	s_nop 0
	v_mul_f32_e32 v46, v48, v46
	v_and_b32_e32 v6, 0xffff0000, v1
	v_pk_add_f32 v[4:5], v[4:5], 1.0 op_sel_hi:[1,0]
	v_and_b32_e32 v54, 0xffff0000, v0
	v_mul_f32_e32 v0, 0xbfb8aa3b, v54
	v_exp_f32_e32 v0, v0
	v_lshlrev_b32_e32 v58, 16, v2
	v_rcp_f32_e32 v49, v5
	s_nop 0
	v_mul_f32_e32 v49, v50, v49
	v_mul_f32_e32 v1, 0xbfb8aa3b, v6
	v_exp_f32_e32 v1, v1
	s_nop 0
	v_pk_add_f32 v[0:1], v[0:1], 1.0 op_sel_hi:[1,0]
	v_rcp_f32_e32 v48, v4
	s_nop 0
	v_mul_f32_e32 v48, v51, v48
	v_lshlrev_b32_e32 v57, 16, v3
	v_rcp_f32_e32 v51, v1
	s_nop 0
	v_mul_f32_e32 v51, v6, v51
	v_add_co_u32_e64 v4, s[4:5], s77, v82
	s_nop 0
	s_nop 0
	v_addc_co_u32_e64 v5, s[4:5], 0, v83, s[4:5]
	global_load_dwordx4 v[4:7], v[4:5], off offset:512
	v_mul_f32_e32 v50, 0xbfb8aa3b, v58
	v_exp_f32_e32 v52, v50
	v_mul_f32_e32 v50, 0xbfb8aa3b, v57
	v_exp_f32_e32 v53, v50
	v_rcp_f32_e32 v50, v0
	s_nop 0
	v_mul_f32_e32 v50, v54, v50
	v_and_b32_e32 v56, 0xffff0000, v3
	v_pk_add_f32 v[0:1], v[52:53], 1.0 op_sel_hi:[1,0]
	v_and_b32_e32 v59, 0xffff0000, v2
	v_mul_f32_e32 v2, 0xbfb8aa3b, v59
	v_exp_f32_e32 v2, v2
	v_rcp_f32_e32 v53, v1
	s_nop 0
	v_mul_f32_e32 v53, v57, v53
	v_mul_f32_e32 v3, 0xbfb8aa3b, v56
	v_exp_f32_e32 v3, v3
	s_nop 0
	v_pk_add_f32 v[54:55], v[2:3], 1.0 op_sel_hi:[1,0]
	v_rcp_f32_e32 v52, v0
	s_nop 0
	v_mul_f32_e32 v52, v58, v52
	v_rcp_f32_e32 v55, v55
	s_nop 0
	v_mul_f32_e32 v55, v56, v55
	v_add_co_u32_e64 v0, s[4:5], s77, v80
	s_waitcnt vmcnt(0)
	v_lshlrev_b32_e32 v62, 16, v5
	v_lshlrev_b32_e32 v63, 16, v4
	v_mul_f32_e32 v56, 0xbfb8aa3b, v63
	v_mul_f32_e32 v57, 0xbfb8aa3b, v62
	v_exp_f32_e32 v56, v56
	v_exp_f32_e32 v57, v57
	v_addc_co_u32_e64 v1, s[4:5], 0, v81, s[4:5]
	v_rcp_f32_e32 v54, v54
	s_nop 0
	v_mul_f32_e32 v54, v59, v54
	v_pk_add_f32 v[56:57], v[56:57], 1.0 op_sel_hi:[1,0]
	v_and_b32_e32 v58, 0xffff0000, v5
	global_load_dwordx4 v[0:3], v[0:1], off offset:512
	v_and_b32_e32 v64, 0xffff0000, v4
	v_mul_f32_e32 v4, 0xbfb8aa3b, v64
	v_rcp_f32_e32 v57, v57
	s_nop 0
	v_mul_f32_e32 v57, v62, v57
	v_exp_f32_e32 v4, v4
	v_mul_f32_e32 v5, 0xbfb8aa3b, v58
	v_exp_f32_e32 v5, v5
	s_nop 0
	v_pk_add_f32 v[4:5], v[4:5], 1.0 op_sel_hi:[1,0]
	v_rcp_f32_e32 v56, v56
	s_nop 0
	v_mul_f32_e32 v56, v63, v56
	v_lshlrev_b32_e32 v65, 16, v6
	v_rcp_f32_e32 v59, v5
	s_nop 0
	v_mul_f32_e32 v59, v58, v59
	v_lshlrev_b32_e32 v62, 16, v7
	v_mul_f32_e32 v60, 0xbfb8aa3b, v65
	v_mul_f32_e32 v61, 0xbfb8aa3b, v62
	v_exp_f32_e32 v60, v60
	v_exp_f32_e32 v61, v61
	v_rcp_f32_e32 v58, v4
	s_nop 0
	v_mul_f32_e32 v58, v64, v58
	v_and_b32_e32 v63, 0xffff0000, v7
	v_pk_add_f32 v[4:5], v[60:61], 1.0 op_sel_hi:[1,0]
	v_and_b32_e32 v64, 0xffff0000, v6
	v_mul_f32_e32 v6, 0xbfb8aa3b, v64
	v_exp_f32_e32 v6, v6
	v_rcp_f32_e32 v61, v5
	s_nop 0
	v_mul_f32_e32 v61, v62, v61
	v_mul_f32_e32 v7, 0xbfb8aa3b, v63
	v_exp_f32_e32 v7, v7
	s_nop 0
	v_pk_add_f32 v[6:7], v[6:7], 1.0 op_sel_hi:[1,0]
	v_rcp_f32_e32 v60, v4
	s_nop 0
	v_mul_f32_e32 v60, v65, v60
	v_rcp_f32_e32 v4, v7
	s_nop 0
	v_mul_f32_e32 v63, v63, v4
	s_waitcnt vmcnt(0)
	v_lshlrev_b32_e32 v66, 16, v1
	v_lshlrev_b32_e32 v67, 16, v0
	v_mul_f32_e32 v4, 0xbfb8aa3b, v67
	v_mul_f32_e32 v5, 0xbfb8aa3b, v66
	v_exp_f32_e32 v4, v4
	v_exp_f32_e32 v5, v5
	v_and_b32_e32 v68, 0xffff0000, v1
	v_rcp_f32_e32 v62, v6
	s_nop 0
	v_mul_f32_e32 v62, v64, v62
	v_pk_add_f32 v[4:5], v[4:5], 1.0 op_sel_hi:[1,0]
	v_and_b32_e32 v69, 0xffff0000, v0
	v_mul_f32_e32 v0, 0xbfb8aa3b, v69
	v_exp_f32_e32 v6, v0
	v_and_b32_e32 v80, 0xffff0000, v2
	v_rcp_f32_e32 v1, v5
	s_nop 0
	v_mul_f32_e32 v1, v66, v1
	v_mul_f32_e32 v7, 0xbfb8aa3b, v68
	v_exp_f32_e32 v7, v7
	s_nop 0
	v_pk_add_f32 v[64:65], v[6:7], 1.0 op_sel_hi:[1,0]
	v_rcp_f32_e32 v0, v4
	s_nop 0
	v_mul_f32_e32 v0, v67, v0
	v_rcp_f32_e32 v65, v65
	s_nop 0
	v_mul_f32_e32 v65, v68, v65
	v_add_co_u32_e64 v4, s[4:5], s77, v78
	s_nop 0
	s_nop 0
	v_addc_co_u32_e64 v5, s[4:5], 0, v79, s[4:5]
	global_load_dwordx4 v[4:7], v[4:5], off offset:512
	v_lshlrev_b32_e32 v78, 16, v3
	v_lshlrev_b32_e32 v79, 16, v2
	v_mul_f32_e32 v66, 0xbfb8aa3b, v79
	v_mul_f32_e32 v67, 0xbfb8aa3b, v78
	v_exp_f32_e32 v66, v66
	v_exp_f32_e32 v67, v67
	v_and_b32_e32 v70, 0xffff0000, v3
	v_rcp_f32_e32 v64, v64
	s_nop 0
	v_mul_f32_e32 v64, v69, v64
	v_pk_add_f32 v[66:67], v[66:67], 1.0 op_sel_hi:[1,0]
	v_mul_f32_e32 v2, 0xbfb8aa3b, v80
	v_exp_f32_e32 v68, v2
	v_mul_f32_e32 v69, 0xbfb8aa3b, v70
	v_exp_f32_e32 v69, v69
	v_rcp_f32_e32 v3, v67
	s_nop 0
	v_mul_f32_e32 v3, v78, v3
	v_pk_add_f32 v[68:69], v[68:69], 1.0 op_sel_hi:[1,0]
	v_rcp_f32_e32 v2, v66
	s_nop 0
	v_mul_f32_e32 v2, v79, v2
	v_rcp_f32_e32 v67, v69
	s_nop 0
	v_mul_f32_e32 v67, v70, v67
	v_add_co_u32_e64 v70, s[4:5], s77, v76
	s_nop 0
	s_nop 0
	v_addc_co_u32_e64 v71, s[4:5], 0, v77, s[4:5]
	global_load_dwordx4 v[76:79], v[70:71], off offset:512
	v_rcp_f32_e32 v66, v68
	s_nop 0
	v_mul_f32_e32 v66, v80, v66
	s_waitcnt vmcnt(1)
	v_lshlrev_b32_e32 v82, 16, v5
	v_lshlrev_b32_e32 v83, 16, v4
	v_mul_f32_e32 v70, 0xbfb8aa3b, v83
	v_mul_f32_e32 v71, 0xbfb8aa3b, v82
	v_exp_f32_e32 v70, v70
	v_exp_f32_e32 v71, v71
	v_and_b32_e32 v80, 0xffff0000, v5
	v_and_b32_e32 v84, 0xffff0000, v4
	v_mul_f32_e32 v4, 0xbfb8aa3b, v84
	v_pk_add_f32 v[68:69], v[70:71], 1.0 op_sel_hi:[1,0]
	v_exp_f32_e32 v70, v4
	s_waitcnt lgkmcnt(0)
	s_barrier
; __device__ __forceinline__ unsigned pack2(float a, float b) { return (unsigned)f2bf(a) | ((unsigned)f2bf(b) << 16); }
; __device__ __forceinline__ float bflo(unsigned w) { return __uint_as_float(w << 16); }
; __device__ __forceinline__ float bfhi(unsigned w) { return __uint_as_float(w & 0xffff0000u); }
; __device__ __forceinline__ float silu_f(float g) { return g / (1.f + __expf(-g)); }
; template <int DH, int MODE>
; __device__ void attn_item(const Params& p, int layer, int b, int blk, int head, char* smem) {
;     ...
; #pragma unroll
;     for (int i = 0; i < NCH; ++i) {
;       int q = tid + 256 * i, r = q / CPR, c = (q % CPR) * 8;
;       float4 m0 = *reinterpret_cast<const float4*>(Of + r * OST + c);
;       float4 m1 = *reinterpret_cast<const float4*>(Of + r * OST + c + 4);
;       float mm[8] = {m0.x, m0.y, m0.z, m0.w, m1.x, m1.y, m1.z, m1.w};
;       unsigned gw[4] = {gt[i].x, gt[i].y, gt[i].z, gt[i].w};
;       unsigned ow[4];
; #pragma unroll
;       for (int e = 0; e < 4; ++e)
;         ow[e] = pack2(mm[2 * e] * silu_f(bflo(gw[e])), mm[2 * e + 1] * silu_f(bfhi(gw[e])));
;       *reinterpret_cast<uint4*>(Y + (tq0 + r) * YW + ycol + c) = make_uint4(ow[0], ow[1], ow[2], ow[3]);
	v_mul_f32_e32 v71, 0xbfb8aa3b, v80
	v_exp_f32_e32 v71, v71
	v_rcp_f32_e32 v5, v69
	s_nop 0
	v_mul_f32_e32 v5, v82, v5
	v_pk_add_f32 v[70:71], v[70:71], 1.0 op_sel_hi:[1,0]
	v_rcp_f32_e32 v4, v68
	s_nop 0
	v_mul_f32_e32 v4, v83, v4
	v_rcp_f32_e32 v69, v71
	s_nop 0
	v_mul_f32_e32 v69, v80, v69
	v_lshlrev_b32_e32 v82, 16, v7
	v_lshlrev_b32_e32 v85, 16, v6
	v_mul_f32_e32 v80, 0xbfb8aa3b, v85
	v_mul_f32_e32 v81, 0xbfb8aa3b, v82
	v_exp_f32_e32 v80, v80
	v_exp_f32_e32 v81, v81
	v_rcp_f32_e32 v68, v70
	s_nop 0
	v_mul_f32_e32 v68, v84, v68
	v_and_b32_e32 v83, 0xffff0000, v7
	v_pk_add_f32 v[70:71], v[80:81], 1.0 op_sel_hi:[1,0]
	v_and_b32_e32 v84, 0xffff0000, v6
	v_mul_f32_e32 v6, 0xbfb8aa3b, v84
	v_exp_f32_e32 v80, v6
	s_waitcnt vmcnt(0)
	v_and_b32_e32 v94, 0xffff0000, v78
	v_mul_f32_e32 v81, 0xbfb8aa3b, v83
	v_exp_f32_e32 v81, v81
	v_rcp_f32_e32 v7, v71
	s_nop 0
	v_mul_f32_e32 v7, v82, v7
	v_pk_add_f32 v[80:81], v[80:81], 1.0 op_sel_hi:[1,0]
	v_rcp_f32_e32 v6, v70
	s_nop 0
	v_mul_f32_e32 v6, v85, v6
	v_rcp_f32_e32 v71, v81
	s_nop 0
	v_mul_f32_e32 v71, v83, v71
	v_lshlrev_b32_e32 v86, 16, v77
	v_lshlrev_b32_e32 v87, 16, v76
	v_mul_f32_e32 v82, 0xbfb8aa3b, v87
	v_mul_f32_e32 v83, 0xbfb8aa3b, v86
	v_exp_f32_e32 v82, v82
	v_exp_f32_e32 v83, v83
	v_rcp_f32_e32 v70, v80
	s_nop 0
	v_mul_f32_e32 v70, v84, v70
	v_and_b32_e32 v88, 0xffff0000, v77
	v_pk_add_f32 v[80:81], v[82:83], 1.0 op_sel_hi:[1,0]
	v_and_b32_e32 v83, 0xffff0000, v76
	v_mul_f32_e32 v76, 0xbfb8aa3b, v83
	v_exp_f32_e32 v76, v76
	v_rcp_f32_e32 v85, v81
	s_nop 0
	v_mul_f32_e32 v85, v86, v85
	v_mul_f32_e32 v77, 0xbfb8aa3b, v88
	v_exp_f32_e32 v77, v77
	s_nop 0
	v_pk_add_f32 v[76:77], v[76:77], 1.0 op_sel_hi:[1,0]
	v_rcp_f32_e32 v84, v80
	s_nop 0
	v_mul_f32_e32 v84, v87, v84
	v_rcp_f32_e32 v87, v77
	s_nop 0
	v_mul_f32_e32 v87, v88, v87
	v_lshlrev_b32_e32 v90, 16, v78
	v_lshlrev_b32_e32 v82, 16, v79
	v_mul_f32_e32 v80, 0xbfb8aa3b, v90
	v_mul_f32_e32 v81, 0xbfb8aa3b, v82
	v_exp_f32_e32 v80, v80
	v_exp_f32_e32 v81, v81
	v_rcp_f32_e32 v86, v76
	s_nop 0
	v_mul_f32_e32 v86, v83, v86
	v_and_b32_e32 v83, 0xffff0000, v79
	v_pk_add_f32 v[76:77], v[80:81], 1.0 op_sel_hi:[1,0]
	v_mul_f32_e32 v78, 0xbfb8aa3b, v94
	v_exp_f32_e32 v78, v78
	v_rcp_f32_e32 v89, v77
	s_nop 0
	v_mul_f32_e32 v89, v82, v89
	v_mul_f32_e32 v79, 0xbfb8aa3b, v83
	v_exp_f32_e32 v79, v79
	s_nop 0
	v_pk_add_f32 v[80:81], v[78:79], 1.0 op_sel_hi:[1,0]
	v_rcp_f32_e32 v88, v76
	s_nop 0
	v_mul_f32_e32 v88, v90, v88
	v_rcp_f32_e32 v91, v81
	s_nop 0
	v_mul_f32_e32 v91, v83, v91
	ds_read_b128 v[76:79], v98
	v_rcp_f32_e32 v90, v80
	s_nop 0
	v_mul_f32_e32 v90, v94, v90
	ds_read_b128 v[80:83], v98 offset:16
	v_add_co_u32_e32 v30, vcc, s74, v30
	s_waitcnt lgkmcnt(1)
	v_mov_b32_e32 v96, v76
	v_mov_b32_e32 v97, v78
	v_pk_mul_f32 v[84:85], v[84:85], v[96:97]
	v_mov_b32_e32 v78, v77
	v_pk_mul_f32 v[76:77], v[86:87], v[78:79]
	v_cvt_pk_bf16_f32 v79, 0, v84
	v_cvt_pk_bf16_f32 v78, 0, v85
	v_cvt_pk_bf16_f32 v77, 0, v77
	v_cvt_pk_bf16_f32 v76, 0, v76
	v_and_b32_e32 v77, 0xffff0000, v77
	v_and_b32_e32 v76, 0xffff0000, v76
	v_or_b32_sdwa v77, v77, v78 dst_sel:DWORD dst_unused:UNUSED_PAD src0_sel:DWORD src1_sel:WORD_1
	v_or_b32_sdwa v76, v76, v79 dst_sel:DWORD dst_unused:UNUSED_PAD src0_sel:DWORD src1_sel:WORD_1
	s_waitcnt lgkmcnt(0)
	v_mov_b32_e32 v78, v80
	v_mov_b32_e32 v79, v82
	v_pk_mul_f32 v[78:79], v[88:89], v[78:79]
	v_mov_b32_e32 v82, v81
	v_pk_mul_f32 v[80:81], v[90:91], v[82:83]
	v_cvt_pk_bf16_f32 v78, 0, v78
	v_cvt_pk_bf16_f32 v79, 0, v79
	v_cvt_pk_bf16_f32 v81, 0, v81
	v_cvt_pk_bf16_f32 v80, 0, v80
	v_and_b32_e32 v81, 0xffff0000, v81
	v_and_b32_e32 v80, 0xffff0000, v80
	v_or_b32_sdwa v79, v81, v79 dst_sel:DWORD dst_unused:UNUSED_PAD src0_sel:DWORD src1_sel:WORD_1
	v_or_b32_sdwa v78, v80, v78 dst_sel:DWORD dst_unused:UNUSED_PAD src0_sel:DWORD src1_sel:WORD_1
	ds_read_b128 v[80:83], v95
	v_addc_co_u32_e32 v31, vcc, 0, v31, vcc
	global_store_dwordx4 v[30:31], v[76:79], off offset:2048
	s_nop 0
	ds_read_b128 v[76:79], v95 offset:16
	s_waitcnt lgkmcnt(1)
	v_mov_b32_e32 v30, v80
	v_mov_b32_e32 v31, v82
	v_pk_mul_f32 v[4:5], v[4:5], v[30:31]
	v_mov_b32_e32 v82, v81
	v_pk_mul_f32 v[30:31], v[68:69], v[82:83]
	v_cvt_pk_bf16_f32 v4, 0, v4
	v_cvt_pk_bf16_f32 v5, 0, v5
	v_cvt_pk_bf16_f32 v31, 0, v31
	v_cvt_pk_bf16_f32 v30, 0, v30
	v_and_b32_e32 v31, 0xffff0000, v31
	v_and_b32_e32 v30, 0xffff0000, v30
	v_or_b32_sdwa v5, v31, v5 dst_sel:DWORD dst_unused:UNUSED_PAD src0_sel:DWORD src1_sel:WORD_1
	v_or_b32_sdwa v4, v30, v4 dst_sel:DWORD dst_unused:UNUSED_PAD src0_sel:DWORD src1_sel:WORD_1
	s_waitcnt lgkmcnt(0)
	v_mov_b32_e32 v30, v76
	v_mov_b32_e32 v31, v78
	v_pk_mul_f32 v[6:7], v[6:7], v[30:31]
	v_mov_b32_e32 v78, v77
	v_pk_mul_f32 v[30:31], v[70:71], v[78:79]
	v_cvt_pk_bf16_f32 v6, 0, v6
	v_cvt_pk_bf16_f32 v7, 0, v7
	v_cvt_pk_bf16_f32 v31, 0, v31
	v_cvt_pk_bf16_f32 v30, 0, v30
	ds_read_b128 v[68:71], v93
	v_and_b32_e32 v31, 0xffff0000, v31
	v_and_b32_e32 v30, 0xffff0000, v30
	v_add_co_u32_e32 v26, vcc, s74, v26
	v_or_b32_sdwa v7, v31, v7 dst_sel:DWORD dst_unused:UNUSED_PAD src0_sel:DWORD src1_sel:WORD_1
	v_or_b32_sdwa v6, v30, v6 dst_sel:DWORD dst_unused:UNUSED_PAD src0_sel:DWORD src1_sel:WORD_1
	v_addc_co_u32_e32 v27, vcc, 0, v27, vcc
	global_store_dwordx4 v[26:27], v[4:7], off offset:2048
	s_waitcnt lgkmcnt(0)
	v_mov_b32_e32 v26, v68
	v_mov_b32_e32 v27, v70
	ds_read_b128 v[4:7], v93 offset:16
	v_pk_mul_f32 v[0:1], v[0:1], v[26:27]
	v_mov_b32_e32 v70, v69
	v_pk_mul_f32 v[26:27], v[64:65], v[70:71]
	v_cvt_pk_bf16_f32 v0, 0, v0
	v_cvt_pk_bf16_f32 v1, 0, v1
	v_cvt_pk_bf16_f32 v27, 0, v27
	v_cvt_pk_bf16_f32 v26, 0, v26
	v_and_b32_e32 v27, 0xffff0000, v27
	v_and_b32_e32 v26, 0xffff0000, v26
	v_or_b32_sdwa v1, v27, v1 dst_sel:DWORD dst_unused:UNUSED_PAD src0_sel:DWORD src1_sel:WORD_1
	v_or_b32_sdwa v0, v26, v0 dst_sel:DWORD dst_unused:UNUSED_PAD src0_sel:DWORD src1_sel:WORD_1
	s_waitcnt lgkmcnt(0)
; __device__ __forceinline__ unsigned pack2(float a, float b) { return (unsigned)f2bf(a) | ((unsigned)f2bf(b) << 16); }
; __device__ __forceinline__ float bflo(unsigned w) { return __uint_as_float(w << 16); }
; __device__ __forceinline__ float bfhi(unsigned w) { return __uint_as_float(w & 0xffff0000u); }
; __device__ __forceinline__ float silu_f(float g) { return g / (1.f + __expf(-g)); }
; template <int DH, int MODE>
; __device__ void attn_item(const Params& p, int layer, int b, int blk, int head, char* smem) {
;     ...
; #pragma unroll
;     for (int i = 0; i < NCH; ++i) {
;       int q = tid + 256 * i, r = q / CPR, c = (q % CPR) * 8;
;       float4 m0 = *reinterpret_cast<const float4*>(Of + r * OST + c);
;       float4 m1 = *reinterpret_cast<const float4*>(Of + r * OST + c + 4);
;       float mm[8] = {m0.x, m0.y, m0.z, m0.w, m1.x, m1.y, m1.z, m1.w};
;       unsigned gw[4] = {gt[i].x, gt[i].y, gt[i].z, gt[i].w};
;       unsigned ow[4];
; #pragma unroll
;       for (int e = 0; e < 4; ++e)
;         ow[e] = pack2(mm[2 * e] * silu_f(bflo(gw[e])), mm[2 * e + 1] * silu_f(bfhi(gw[e])));
;       *reinterpret_cast<uint4*>(Y + (tq0 + r) * YW + ycol + c) = make_uint4(ow[0], ow[1], ow[2], ow[3]);
	v_mov_b32_e32 v26, v4
	v_mov_b32_e32 v27, v6
	v_pk_mul_f32 v[2:3], v[2:3], v[26:27]
	v_mov_b32_e32 v6, v5
	v_pk_mul_f32 v[4:5], v[66:67], v[6:7]
	v_cvt_pk_bf16_f32 v2, 0, v2
	v_cvt_pk_bf16_f32 v3, 0, v3
	v_cvt_pk_bf16_f32 v5, 0, v5
	v_cvt_pk_bf16_f32 v4, 0, v4
	v_and_b32_e32 v5, 0xffff0000, v5
	v_and_b32_e32 v4, 0xffff0000, v4
	v_or_b32_sdwa v3, v5, v3 dst_sel:DWORD dst_unused:UNUSED_PAD src0_sel:DWORD src1_sel:WORD_1
	v_or_b32_sdwa v2, v4, v2 dst_sel:DWORD dst_unused:UNUSED_PAD src0_sel:DWORD src1_sel:WORD_1
	ds_read_b128 v[4:7], v92
	v_add_co_u32_e32 v20, vcc, s74, v20
	s_nop 1
	v_addc_co_u32_e32 v21, vcc, 0, v21, vcc
	global_store_dwordx4 v[20:21], v[0:3], off offset:2048
	s_waitcnt lgkmcnt(0)
	v_mov_b32_e32 v20, v4
	v_mov_b32_e32 v21, v6
	ds_read_b128 v[0:3], v92 offset:16
	v_pk_mul_f32 v[20:21], v[56:57], v[20:21]
	v_mov_b32_e32 v6, v5
	v_pk_mul_f32 v[4:5], v[58:59], v[6:7]
	v_cvt_pk_bf16_f32 v7, 0, v20
	v_cvt_pk_bf16_f32 v6, 0, v21
	v_cvt_pk_bf16_f32 v5, 0, v5
	v_cvt_pk_bf16_f32 v4, 0, v4
	v_and_b32_e32 v5, 0xffff0000, v5
	v_and_b32_e32 v4, 0xffff0000, v4
	v_or_b32_sdwa v5, v5, v6 dst_sel:DWORD dst_unused:UNUSED_PAD src0_sel:DWORD src1_sel:WORD_1
	v_or_b32_sdwa v4, v4, v7 dst_sel:DWORD dst_unused:UNUSED_PAD src0_sel:DWORD src1_sel:WORD_1
	s_waitcnt lgkmcnt(0)
	v_mov_b32_e32 v6, v0
	v_mov_b32_e32 v7, v2
	v_pk_mul_f32 v[6:7], v[60:61], v[6:7]
	v_mov_b32_e32 v2, v1
	v_pk_mul_f32 v[0:1], v[62:63], v[2:3]
	v_cvt_pk_bf16_f32 v3, 0, v6
	v_cvt_pk_bf16_f32 v2, 0, v7
	v_cvt_pk_bf16_f32 v1, 0, v1
	v_cvt_pk_bf16_f32 v0, 0, v0
	v_and_b32_e32 v1, 0xffff0000, v1
	v_and_b32_e32 v0, 0xffff0000, v0
	v_or_b32_sdwa v7, v1, v2 dst_sel:DWORD dst_unused:UNUSED_PAD src0_sel:DWORD src1_sel:WORD_1
	v_or_b32_sdwa v6, v0, v3 dst_sel:DWORD dst_unused:UNUSED_PAD src0_sel:DWORD src1_sel:WORD_1
	ds_read_b128 v[0:3], v75
	v_add_co_u32_e32 v16, vcc, s74, v16
	s_nop 1
	v_addc_co_u32_e32 v17, vcc, 0, v17, vcc
	global_store_dwordx4 v[16:17], v[4:7], off offset:2048
	s_waitcnt lgkmcnt(0)
	v_mov_b32_e32 v16, v0
	v_mov_b32_e32 v17, v2
	ds_read_b128 v[4:7], v75 offset:16
	v_pk_mul_f32 v[16:17], v[48:49], v[16:17]
	v_mov_b32_e32 v2, v1
	v_pk_mul_f32 v[0:1], v[50:51], v[2:3]
	v_cvt_pk_bf16_f32 v3, 0, v16
	v_cvt_pk_bf16_f32 v2, 0, v17
	v_cvt_pk_bf16_f32 v1, 0, v1
	v_cvt_pk_bf16_f32 v0, 0, v0
	v_and_b32_e32 v1, 0xffff0000, v1
	v_and_b32_e32 v0, 0xffff0000, v0
	v_or_b32_sdwa v1, v1, v2 dst_sel:DWORD dst_unused:UNUSED_PAD src0_sel:DWORD src1_sel:WORD_1
	v_or_b32_sdwa v0, v0, v3 dst_sel:DWORD dst_unused:UNUSED_PAD src0_sel:DWORD src1_sel:WORD_1
	s_waitcnt lgkmcnt(0)
	v_mov_b32_e32 v2, v4
	v_mov_b32_e32 v3, v6
	v_pk_mul_f32 v[2:3], v[52:53], v[2:3]
	v_mov_b32_e32 v6, v5
	v_pk_mul_f32 v[4:5], v[54:55], v[6:7]
	v_cvt_pk_bf16_f32 v2, 0, v2
	v_cvt_pk_bf16_f32 v3, 0, v3
	v_cvt_pk_bf16_f32 v5, 0, v5
	v_cvt_pk_bf16_f32 v4, 0, v4
	v_and_b32_e32 v5, 0xffff0000, v5
	v_and_b32_e32 v4, 0xffff0000, v4
	v_or_b32_sdwa v3, v5, v3 dst_sel:DWORD dst_unused:UNUSED_PAD src0_sel:DWORD src1_sel:WORD_1
	v_or_b32_sdwa v2, v4, v2 dst_sel:DWORD dst_unused:UNUSED_PAD src0_sel:DWORD src1_sel:WORD_1
	ds_read_b128 v[4:7], v74
	v_add_co_u32_e32 v12, vcc, s74, v12
	s_nop 1
	v_addc_co_u32_e32 v13, vcc, 0, v13, vcc
	global_store_dwordx4 v[12:13], v[0:3], off offset:2048
	s_waitcnt lgkmcnt(0)
; __device__ __forceinline__ unsigned pack2(float a, float b) { return (unsigned)f2bf(a) | ((unsigned)f2bf(b) << 16); }
; __device__ __forceinline__ float bflo(unsigned w) { return __uint_as_float(w << 16); }
; __device__ __forceinline__ float bfhi(unsigned w) { return __uint_as_float(w & 0xffff0000u); }
; __device__ __forceinline__ float silu_f(float g) { return g / (1.f + __expf(-g)); }
; template <int DH, int MODE>
; __device__ void attn_item(const Params& p, int layer, int b, int blk, int head, char* smem) {
;     ...
; #pragma unroll
;     for (int i = 0; i < NCH; ++i) {
;       int q = tid + 256 * i, r = q / CPR, c = (q % CPR) * 8;
;       float4 m0 = *reinterpret_cast<const float4*>(Of + r * OST + c);
;       float4 m1 = *reinterpret_cast<const float4*>(Of + r * OST + c + 4);
;       float mm[8] = {m0.x, m0.y, m0.z, m0.w, m1.x, m1.y, m1.z, m1.w};
;       unsigned gw[4] = {gt[i].x, gt[i].y, gt[i].z, gt[i].w};
;       unsigned ow[4];
; #pragma unroll
;       for (int e = 0; e < 4; ++e)
;         ow[e] = pack2(mm[2 * e] * silu_f(bflo(gw[e])), mm[2 * e + 1] * silu_f(bfhi(gw[e])));
;       *reinterpret_cast<uint4*>(Y + (tq0 + r) * YW + ycol + c) = make_uint4(ow[0], ow[1], ow[2], ow[3]);
;     }
;   }
;   __syncthreads();
	v_mov_b32_e32 v12, v4
	v_mov_b32_e32 v13, v6
	ds_read_b128 v[0:3], v74 offset:16
	v_pk_mul_f32 v[12:13], v[40:41], v[12:13]
	v_mov_b32_e32 v6, v5
	v_pk_mul_f32 v[4:5], v[42:43], v[6:7]
	v_cvt_pk_bf16_f32 v7, 0, v12
	v_cvt_pk_bf16_f32 v6, 0, v13
	v_cvt_pk_bf16_f32 v5, 0, v5
	v_cvt_pk_bf16_f32 v4, 0, v4
	v_and_b32_e32 v5, 0xffff0000, v5
	v_and_b32_e32 v4, 0xffff0000, v4
	v_or_b32_sdwa v5, v5, v6 dst_sel:DWORD dst_unused:UNUSED_PAD src0_sel:DWORD src1_sel:WORD_1
	v_or_b32_sdwa v4, v4, v7 dst_sel:DWORD dst_unused:UNUSED_PAD src0_sel:DWORD src1_sel:WORD_1
	s_waitcnt lgkmcnt(0)
	v_mov_b32_e32 v6, v0
	v_mov_b32_e32 v7, v2
	v_pk_mul_f32 v[6:7], v[44:45], v[6:7]
	v_mov_b32_e32 v2, v1
	v_pk_mul_f32 v[0:1], v[46:47], v[2:3]
	v_cvt_pk_bf16_f32 v3, 0, v6
	v_cvt_pk_bf16_f32 v2, 0, v7
	v_cvt_pk_bf16_f32 v1, 0, v1
	v_cvt_pk_bf16_f32 v0, 0, v0
	v_and_b32_e32 v1, 0xffff0000, v1
	v_and_b32_e32 v0, 0xffff0000, v0
	v_or_b32_sdwa v7, v1, v2 dst_sel:DWORD dst_unused:UNUSED_PAD src0_sel:DWORD src1_sel:WORD_1
	v_or_b32_sdwa v6, v0, v3 dst_sel:DWORD dst_unused:UNUSED_PAD src0_sel:DWORD src1_sel:WORD_1
	ds_read_b128 v[0:3], v73
	v_add_co_u32_e32 v10, vcc, s74, v10
	s_nop 1
	v_addc_co_u32_e32 v11, vcc, 0, v11, vcc
	global_store_dwordx4 v[10:11], v[4:7], off offset:2048
	s_waitcnt lgkmcnt(0)
	v_mov_b32_e32 v10, v0
	v_mov_b32_e32 v11, v2
	ds_read_b128 v[4:7], v73 offset:16
	v_pk_mul_f32 v[10:11], v[32:33], v[10:11]
	v_mov_b32_e32 v2, v1
	v_pk_mul_f32 v[0:1], v[34:35], v[2:3]
	v_cvt_pk_bf16_f32 v3, 0, v10
	v_cvt_pk_bf16_f32 v2, 0, v11
	v_cvt_pk_bf16_f32 v1, 0, v1
	v_cvt_pk_bf16_f32 v0, 0, v0
	v_and_b32_e32 v1, 0xffff0000, v1
	v_and_b32_e32 v0, 0xffff0000, v0
	v_or_b32_sdwa v1, v1, v2 dst_sel:DWORD dst_unused:UNUSED_PAD src0_sel:DWORD src1_sel:WORD_1
	v_or_b32_sdwa v0, v0, v3 dst_sel:DWORD dst_unused:UNUSED_PAD src0_sel:DWORD src1_sel:WORD_1
	s_waitcnt lgkmcnt(0)
	v_mov_b32_e32 v2, v4
	v_mov_b32_e32 v3, v6
	v_pk_mul_f32 v[2:3], v[36:37], v[2:3]
	v_mov_b32_e32 v6, v5
	v_pk_mul_f32 v[4:5], v[38:39], v[6:7]
	v_cvt_pk_bf16_f32 v2, 0, v2
	v_cvt_pk_bf16_f32 v3, 0, v3
	v_cvt_pk_bf16_f32 v5, 0, v5
	v_cvt_pk_bf16_f32 v4, 0, v4
	v_and_b32_e32 v5, 0xffff0000, v5
	v_and_b32_e32 v4, 0xffff0000, v4
	v_or_b32_sdwa v3, v5, v3 dst_sel:DWORD dst_unused:UNUSED_PAD src0_sel:DWORD src1_sel:WORD_1
	v_or_b32_sdwa v2, v4, v2 dst_sel:DWORD dst_unused:UNUSED_PAD src0_sel:DWORD src1_sel:WORD_1
	ds_read_b128 v[4:7], v72
	v_add_co_u32_e32 v8, vcc, s74, v8
	s_nop 1
	v_addc_co_u32_e32 v9, vcc, 0, v9, vcc
	global_store_dwordx4 v[8:9], v[0:3], off offset:2048
	s_waitcnt lgkmcnt(0)
	v_mov_b32_e32 v8, v4
	v_mov_b32_e32 v9, v6
	ds_read_b128 v[0:3], v72 offset:16
	v_pk_mul_f32 v[8:9], v[18:19], v[8:9]
	v_mov_b32_e32 v6, v5
	v_pk_mul_f32 v[4:5], v[22:23], v[6:7]
	v_cvt_pk_bf16_f32 v7, 0, v8
	v_cvt_pk_bf16_f32 v6, 0, v9
	v_cvt_pk_bf16_f32 v5, 0, v5
	v_cvt_pk_bf16_f32 v4, 0, v4
	v_and_b32_e32 v5, 0xffff0000, v5
	v_and_b32_e32 v4, 0xffff0000, v4
	v_or_b32_sdwa v5, v5, v6 dst_sel:DWORD dst_unused:UNUSED_PAD src0_sel:DWORD src1_sel:WORD_1
	v_or_b32_sdwa v4, v4, v7 dst_sel:DWORD dst_unused:UNUSED_PAD src0_sel:DWORD src1_sel:WORD_1
	s_waitcnt lgkmcnt(0)
	v_mov_b32_e32 v6, v0
	v_mov_b32_e32 v7, v2
	v_pk_mul_f32 v[6:7], v[24:25], v[6:7]
	v_mov_b32_e32 v2, v1
	v_pk_mul_f32 v[0:1], v[28:29], v[2:3]
	v_cvt_pk_bf16_f32 v2, 0, v7
	v_cvt_pk_bf16_f32 v3, 0, v6
	v_cvt_pk_bf16_f32 v0, 0, v0
	v_cvt_pk_bf16_f32 v1, 0, v1
	v_and_b32_e32 v0, 0xffff0000, v0
	v_and_b32_e32 v1, 0xffff0000, v1
	v_or_b32_sdwa v6, v0, v3 dst_sel:DWORD dst_unused:UNUSED_PAD src0_sel:DWORD src1_sel:WORD_1
	v_add_co_u32_e32 v0, vcc, 0x184a1000, v14
	v_or_b32_sdwa v7, v1, v2 dst_sel:DWORD dst_unused:UNUSED_PAD src0_sel:DWORD src1_sel:WORD_1
	s_nop 0
	v_addc_co_u32_e32 v1, vcc, 0, v15, vcc
	global_store_dwordx4 v[0:1], v[4:7], off offset:2048
	s_barrier

; __device__ __forceinline__ float bflo(unsigned w) { return __uint_as_float(w << 16); }
; __device__ __forceinline__ float bfhi(unsigned w) { return __uint_as_float(w & 0xffff0000u); }
; __device__ void gmlp_item(const Params& p, int layer, int b, int n, int g, char* smem) {
;     ...
;   {
;     uint4 raw[8];
; #pragma unroll
;     for (int i = 0; i < 8; ++i) {
;       int q = tid + 256 * i;
;       int st = q & 127, c0 = (q >> 7) * 8;
;       raw[i] = *reinterpret_cast<const uint4*>(P + (t0 + st) * NP + 512 + g * 128 + c0);
;     }
; #pragma unroll
;     for (int i = 0; i < 8; ++i) {
;       int q = tid + 256 * i;
;       int st = q & 127, c0 = (q >> 7) * 8;
;       unsigned w[4] = {raw[i].x, raw[i].y, raw[i].z, raw[i].w};
;       float mu = mu_s[st], rs = rs_s[st];
;       const float4* gp = reinterpret_cast<const float4*>(p.gm_gain + (size_t)layer * 512 + g * 128 + c0);
;       float4 g0 = gp[0], g1 = gp[1];
;       float gg[8] = {g0.x, g0.y, g0.z, g0.w, g1.x, g1.y, g1.z, g1.w};
; #pragma unroll
;       for (int e = 0; e < 8; ++e) {
;         float v = (e & 1) ? bfhi(w[e >> 1]) : bflo(w[e >> 1]);
;         float val = (v - mu) * rs * gg[e];
;         *reinterpret_cast<u16*>(smem + 32768 + (st >> 5) * 8192 + (c0 + e) * 64 + (st & 31) * 2) = f2bf(val);
;       }
;     }
.LBB0_158:
	s_or_b64 exec, exec, s[6:7]
	v_and_b32_e32 v6, 0x7f, v60
	s_ashr_i32 s6, s8, 31
	s_bfe_u32 s10, s79, 0x20003
	s_waitcnt lgkmcnt(0)
	v_or_b32_e32 v0, s26, v6
	s_add_u32 s11, s28, s8
	v_mul_lo_u32 v128, v0, s64
	v_ashrrev_i32_e32 v34, 4, v60
	s_addc_u32 s48, s29, s6
	v_lshl_add_u64 v[0:1], v[128:129], 1, s[4:5]
	s_lshl_b32 s6, s10, 8
	s_mov_b32 s7, s27
	v_and_b32_e32 v2, -8, v34
	v_lshl_add_u64 v[0:1], v[0:1], 0, s[6:7]
	v_ashrrev_i32_e32 v3, 31, v2
	v_lshl_add_u64 v[4:5], v[2:3], 1, v[0:1]
	s_barrier
	global_load_dwordx4 v[28:31], v[4:5], off offset:1024
	s_lshl_b32 s8, s10, 7
	s_lshl_b32 s6, s10, 9
	s_add_u32 s6, s14, s6
	s_addc_u32 s7, s15, 0
	v_lshl_add_u64 v[4:5], v[2:3], 2, s[6:7]
	global_load_dwordx4 v[62:65], v[4:5], off
	global_load_dwordx4 v[66:69], v[4:5], off offset:16
	v_add_u32_e32 v3, 0x100, v60
	v_ashrrev_i32_e32 v48, 4, v3
	v_add_u32_e32 v4, 0x200, v60
	v_lshlrev_b32_e32 v12, 1, v60
	v_and_b32_e32 v82, -8, v48
	v_add_u32_e32 v5, 0x300, v60
	v_lshlrev_b32_e32 v11, 8, v60
	v_ashrrev_i32_e32 v46, 4, v4
	v_and_b32_e32 v4, 62, v12
	v_ashrrev_i32_e32 v83, 31, v82
	v_ashrrev_i32_e32 v44, 4, v5
	v_and_or_b32 v37, v11, s65, v4
	v_lshl_add_u64 v[4:5], v[82:83], 1, v[0:1]
	global_load_dwordx4 v[24:27], v[4:5], off offset:1024
	v_lshl_add_u64 v[4:5], v[82:83], 2, s[6:7]
	global_load_dwordx4 v[70:73], v[4:5], off offset:16
	global_load_dwordx4 v[74:77], v[4:5], off
	v_lshlrev_b32_e32 v3, 2, v6
	v_or_b32_e32 v6, 0x10000, v3
	v_or_b32_e32 v3, 0x10200, v3
	ds_read_b32 v39, v6
	ds_read_b32 v41, v3
	v_add_u32_e32 v7, 0x400, v60
	v_add_u32_e32 v8, 0x500, v60
	v_add_u32_e32 v9, 0x600, v60
	v_add_u32_e32 v10, 0x700, v60
	v_ashrrev_i32_e32 v42, 4, v7
	v_ashrrev_i32_e32 v40, 4, v8
	v_ashrrev_i32_e32 v38, 4, v9
	v_ashrrev_i32_e32 v36, 4, v10
	v_and_b32_e32 v58, -8, v46
	v_and_b32_e32 v56, -8, v44
	v_and_b32_e32 v54, -8, v42
	v_and_b32_e32 v52, -8, v40
	v_and_b32_e32 v50, -8, v38
	v_and_b32_e32 v32, -8, v36
	v_ashrrev_i32_e32 v59, 31, v58
	v_ashrrev_i32_e32 v57, 31, v56
	v_ashrrev_i32_e32 v55, 31, v54
	v_ashrrev_i32_e32 v53, 31, v52
	v_ashrrev_i32_e32 v51, 31, v50
	v_ashrrev_i32_e32 v33, 31, v32
	v_lshl_add_u32 v43, v2, 6, v37
	v_lshl_add_u64 v[2:3], v[58:59], 1, v[0:1]
	v_lshl_add_u64 v[4:5], v[56:57], 1, v[0:1]
	v_lshl_add_u64 v[6:7], v[54:55], 1, v[0:1]
	v_lshl_add_u64 v[8:9], v[52:53], 1, v[0:1]
	v_lshl_add_u64 v[78:79], v[50:51], 1, v[0:1]
	v_lshl_add_u64 v[0:1], v[32:33], 1, v[0:1]
	global_load_dwordx4 v[20:23], v[2:3], off offset:1024
	global_load_dwordx4 v[16:19], v[4:5], off offset:1024
	global_load_dwordx4 v[12:15], v[6:7], off offset:1024
	s_nop 0
	global_load_dwordx4 v[8:11], v[8:9], off offset:1024
	s_nop 0
	global_load_dwordx4 v[4:7], v[78:79], off offset:1024
	s_nop 0
	global_load_dwordx4 v[0:3], v[0:1], off offset:1024
	v_and_b32_e32 v35, 15, v60
	v_lshlrev_b32_e32 v128, 4, v35
	s_waitcnt vmcnt(11)
	v_lshlrev_b32_e32 v45, 16, v28
	s_waitcnt lgkmcnt(1)
	v_sub_f32_e32 v45, v45, v39
	v_and_b32_e32 v28, 0xffff0000, v28
	s_waitcnt lgkmcnt(0)
	v_mul_f32_e32 v45, v41, v45
	v_sub_f32_e32 v28, v28, v39
	s_waitcnt vmcnt(10)
	v_mul_f32_e32 v45, v45, v62
	v_mul_f32_e32 v28, v41, v28
	v_mul_f32_e32 v28, v28, v63
	v_cvt_pk_bf16_f32 v45, 0, v45
	ds_write_b16_d16_hi v43, v45 offset:32768
	v_cvt_pk_bf16_f32 v28, 0, v28
	ds_write_b16_d16_hi v43, v28 offset:32832
	v_lshlrev_b32_e32 v28, 16, v29
	v_sub_f32_e32 v28, v28, v39
	v_mul_f32_e32 v28, v41, v28
	v_mul_f32_e32 v28, v28, v64
	v_cvt_pk_bf16_f32 v28, 0, v28
	ds_write_b16_d16_hi v43, v28 offset:32896
	v_and_b32_e32 v28, 0xffff0000, v29
	v_sub_f32_e32 v28, v28, v39
	v_mul_f32_e32 v28, v41, v28
	v_mul_f32_e32 v28, v28, v65
	v_cvt_pk_bf16_f32 v28, 0, v28
	ds_write_b16_d16_hi v43, v28 offset:32960
	v_lshlrev_b32_e32 v28, 16, v30
	v_sub_f32_e32 v28, v28, v39
	v_mul_f32_e32 v28, v41, v28
	s_waitcnt vmcnt(9)
	v_mul_f32_e32 v28, v28, v66
	v_cvt_pk_bf16_f32 v28, 0, v28
	ds_write_b16_d16_hi v43, v28 offset:33024
	v_and_b32_e32 v28, 0xffff0000, v30
	v_sub_f32_e32 v28, v28, v39
	v_mul_f32_e32 v28, v41, v28
	v_mul_f32_e32 v28, v28, v67
	v_cvt_pk_bf16_f32 v28, 0, v28
	ds_write_b16_d16_hi v43, v28 offset:33088
	v_lshlrev_b32_e32 v28, 16, v31
	v_sub_f32_e32 v30, v28, v39
	v_lshl_add_u64 v[28:29], v[58:59], 2, s[6:7]
	global_load_dwordx4 v[62:65], v[28:29], off offset:16
	global_load_dwordx4 v[78:81], v[28:29], off
	v_mul_f32_e32 v28, v41, v30
	v_mul_f32_e32 v28, v28, v68
	v_cvt_pk_bf16_f32 v28, 0, v28
	ds_write_b16_d16_hi v43, v28 offset:33152
	v_and_b32_e32 v28, 0xffff0000, v31
	v_sub_f32_e32 v28, v28, v39
	v_mul_f32_e32 v28, v41, v28
	v_mul_f32_e32 v28, v28, v69
	v_cvt_pk_bf16_f32 v28, 0, v28
	v_lshl_or_b32 v29, v34, 6, v159
	v_add_u32_e32 v29, v37, v29
	ds_write_b16_d16_hi v29, v28 offset:32768
	s_waitcnt vmcnt(10)
	v_lshlrev_b32_e32 v28, 16, v24
	v_sub_f32_e32 v28, v28, v39
	v_mul_f32_e32 v28, v41, v28
	v_and_b32_e32 v24, 0xffff0000, v24
	s_waitcnt vmcnt(8)
; __device__ __forceinline__ float bflo(unsigned w) { return __uint_as_float(w << 16); }
; __device__ __forceinline__ float bfhi(unsigned w) { return __uint_as_float(w & 0xffff0000u); }
; __device__ void gmlp_item(const Params& p, int layer, int b, int n, int g, char* smem) {
;     ...
; #pragma unroll
;     for (int i = 0; i < 8; ++i) {
;       int q = tid + 256 * i;
;       int st = q & 127, c0 = (q >> 7) * 8;
;       unsigned w[4] = {raw[i].x, raw[i].y, raw[i].z, raw[i].w};
;       float mu = mu_s[st], rs = rs_s[st];
;       const float4* gp = reinterpret_cast<const float4*>(p.gm_gain + (size_t)layer * 512 + g * 128 + c0);
;       float4 g0 = gp[0], g1 = gp[1];
;       float gg[8] = {g0.x, g0.y, g0.z, g0.w, g1.x, g1.y, g1.z, g1.w};
; #pragma unroll
;       for (int e = 0; e < 8; ++e) {
;         float v = (e & 1) ? bfhi(w[e >> 1]) : bflo(w[e >> 1]);
;         float val = (v - mu) * rs * gg[e];
;         *reinterpret_cast<u16*>(smem + 32768 + (st >> 5) * 8192 + (c0 + e) * 64 + (st & 31) * 2) = f2bf(val);
;       }
;     }
	v_mul_f32_e32 v28, v28, v74
	v_sub_f32_e32 v24, v24, v39
	v_mul_f32_e32 v24, v41, v24
	v_cvt_pk_bf16_f32 v28, 0, v28
	v_lshl_add_u32 v43, v82, 6, v37
	v_mul_f32_e32 v24, v24, v75
	ds_write_b16_d16_hi v43, v28 offset:32768
	v_cvt_pk_bf16_f32 v24, 0, v24
	ds_write_b16_d16_hi v43, v24 offset:32832
	v_lshlrev_b32_e32 v24, 16, v25
	v_sub_f32_e32 v24, v24, v39
	v_mul_f32_e32 v24, v41, v24
	v_mul_f32_e32 v24, v24, v76
	v_cvt_pk_bf16_f32 v24, 0, v24
	ds_write_b16_d16_hi v43, v24 offset:32896
	v_and_b32_e32 v24, 0xffff0000, v25
	v_sub_f32_e32 v24, v24, v39
	v_mul_f32_e32 v24, v41, v24
	v_mul_f32_e32 v24, v24, v77
	v_cvt_pk_bf16_f32 v24, 0, v24
	ds_write_b16_d16_hi v43, v24 offset:32960
	v_lshlrev_b32_e32 v24, 16, v26
	v_sub_f32_e32 v24, v24, v39
	v_mul_f32_e32 v24, v41, v24
	v_mul_f32_e32 v24, v24, v70
	v_cvt_pk_bf16_f32 v24, 0, v24
	ds_write_b16_d16_hi v43, v24 offset:33024
	v_and_b32_e32 v24, 0xffff0000, v26
	v_sub_f32_e32 v24, v24, v39
	v_mul_f32_e32 v24, v41, v24
	v_mul_f32_e32 v24, v24, v71
	v_cvt_pk_bf16_f32 v24, 0, v24
	ds_write_b16_d16_hi v43, v24 offset:33088
	v_lshlrev_b32_e32 v24, 16, v27
	v_sub_f32_e32 v26, v24, v39
	v_lshl_add_u64 v[24:25], v[56:57], 2, s[6:7]
	global_load_dwordx4 v[28:31], v[24:25], off offset:16
	global_load_dwordx4 v[66:69], v[24:25], off
	v_mul_f32_e32 v24, v41, v26
	v_mul_f32_e32 v24, v24, v72
	v_cvt_pk_bf16_f32 v24, 0, v24
	ds_write_b16_d16_hi v43, v24 offset:33152
	v_and_b32_e32 v24, 0xffff0000, v27
	v_sub_f32_e32 v24, v24, v39
	v_mul_f32_e32 v24, v41, v24
	v_mul_f32_e32 v24, v24, v73
	v_cvt_pk_bf16_f32 v24, 0, v24
	v_lshl_or_b32 v25, v48, 6, v159
	v_add_u32_e32 v25, v37, v25
	ds_write_b16_d16_hi v25, v24 offset:32768
	s_waitcnt vmcnt(9)
	v_lshlrev_b32_e32 v24, 16, v20
	v_sub_f32_e32 v24, v24, v39
	v_mul_f32_e32 v24, v41, v24
	v_and_b32_e32 v20, 0xffff0000, v20
	s_waitcnt vmcnt(2)
	v_mul_f32_e32 v24, v24, v78
	v_sub_f32_e32 v20, v20, v39
	v_mul_f32_e32 v20, v41, v20
	v_cvt_pk_bf16_f32 v24, 0, v24
	v_lshl_add_u32 v43, v58, 6, v37
	v_mul_f32_e32 v20, v20, v79
	ds_write_b16_d16_hi v43, v24 offset:32768
	v_cvt_pk_bf16_f32 v20, 0, v20
	ds_write_b16_d16_hi v43, v20 offset:32832
	v_lshlrev_b32_e32 v20, 16, v21
	v_sub_f32_e32 v20, v20, v39
	v_mul_f32_e32 v20, v41, v20
	v_mul_f32_e32 v20, v20, v80
	v_cvt_pk_bf16_f32 v20, 0, v20
	ds_write_b16_d16_hi v43, v20 offset:32896
	v_and_b32_e32 v20, 0xffff0000, v21
	v_sub_f32_e32 v20, v20, v39
	v_mul_f32_e32 v20, v41, v20
	v_mul_f32_e32 v20, v20, v81
	v_cvt_pk_bf16_f32 v20, 0, v20
	ds_write_b16_d16_hi v43, v20 offset:32960
	v_lshlrev_b32_e32 v20, 16, v22
	v_sub_f32_e32 v20, v20, v39
	v_mul_f32_e32 v20, v41, v20
	v_mul_f32_e32 v20, v20, v62
	v_cvt_pk_bf16_f32 v20, 0, v20
	ds_write_b16_d16_hi v43, v20 offset:33024
	v_and_b32_e32 v20, 0xffff0000, v22
	v_sub_f32_e32 v20, v20, v39
	v_mul_f32_e32 v20, v41, v20
	v_mul_f32_e32 v20, v20, v63
	v_cvt_pk_bf16_f32 v20, 0, v20
	ds_write_b16_d16_hi v43, v20 offset:33088
	v_lshlrev_b32_e32 v20, 16, v23
	v_sub_f32_e32 v22, v20, v39
	v_lshl_add_u64 v[20:21], v[54:55], 2, s[6:7]
	global_load_dwordx4 v[24:27], v[20:21], off offset:16
	global_load_dwordx4 v[70:73], v[20:21], off
	v_mul_f32_e32 v20, v41, v22
	v_mul_f32_e32 v20, v20, v64
	v_cvt_pk_bf16_f32 v20, 0, v20
	ds_write_b16_d16_hi v43, v20 offset:33152
	v_and_b32_e32 v20, 0xffff0000, v23
	v_sub_f32_e32 v20, v20, v39
	v_mul_f32_e32 v20, v41, v20
	v_mul_f32_e32 v20, v20, v65
	v_cvt_pk_bf16_f32 v20, 0, v20
	v_lshl_or_b32 v21, v46, 6, v159
	v_add_u32_e32 v21, v37, v21
	ds_write_b16_d16_hi v21, v20 offset:32768
	v_lshlrev_b32_e32 v20, 16, v16
	v_sub_f32_e32 v20, v20, v39
	v_mul_f32_e32 v20, v41, v20
	v_and_b32_e32 v16, 0xffff0000, v16
	s_waitcnt vmcnt(2)
	v_mul_f32_e32 v20, v20, v66
	v_sub_f32_e32 v16, v16, v39
	v_mul_f32_e32 v16, v41, v16
	v_cvt_pk_bf16_f32 v20, 0, v20
	v_lshl_add_u32 v43, v56, 6, v37
	v_mul_f32_e32 v16, v16, v67
	ds_write_b16_d16_hi v43, v20 offset:32768
	v_cvt_pk_bf16_f32 v16, 0, v16
	ds_write_b16_d16_hi v43, v16 offset:32832
	v_lshlrev_b32_e32 v16, 16, v17
	v_sub_f32_e32 v16, v16, v39
	v_mul_f32_e32 v16, v41, v16
	v_mul_f32_e32 v16, v16, v68
	v_cvt_pk_bf16_f32 v16, 0, v16
	ds_write_b16_d16_hi v43, v16 offset:32896
	v_and_b32_e32 v16, 0xffff0000, v17
	v_sub_f32_e32 v16, v16, v39
	v_mul_f32_e32 v16, v41, v16
	v_mul_f32_e32 v16, v16, v69
	v_cvt_pk_bf16_f32 v16, 0, v16
	ds_write_b16_d16_hi v43, v16 offset:32960
	v_lshlrev_b32_e32 v16, 16, v18
	v_sub_f32_e32 v16, v16, v39
	v_mul_f32_e32 v16, v41, v16
	v_mul_f32_e32 v16, v16, v28
	v_cvt_pk_bf16_f32 v16, 0, v16
	ds_write_b16_d16_hi v43, v16 offset:33024
	v_and_b32_e32 v16, 0xffff0000, v18
	v_sub_f32_e32 v16, v16, v39
	v_mul_f32_e32 v16, v41, v16
	v_mul_f32_e32 v16, v16, v29
	v_cvt_pk_bf16_f32 v16, 0, v16
	ds_write_b16_d16_hi v43, v16 offset:33088
	v_lshlrev_b32_e32 v16, 16, v19
	v_sub_f32_e32 v18, v16, v39
	v_lshl_add_u64 v[16:17], v[52:53], 2, s[6:7]
	global_load_dwordx4 v[20:23], v[16:17], off offset:16
	global_load_dwordx4 v[56:59], v[16:17], off
	v_mul_f32_e32 v16, v41, v18
	v_mul_f32_e32 v16, v16, v30
	v_cvt_pk_bf16_f32 v16, 0, v16
	ds_write_b16_d16_hi v43, v16 offset:33152
	v_and_b32_e32 v16, 0xffff0000, v19
	v_sub_f32_e32 v16, v16, v39
	v_mul_f32_e32 v16, v41, v16
	v_mul_f32_e32 v16, v16, v31
	v_cvt_pk_bf16_f32 v16, 0, v16
	v_lshl_or_b32 v17, v44, 6, v159
	v_add_u32_e32 v17, v37, v17
	ds_write_b16_d16_hi v17, v16 offset:32768
	v_lshlrev_b32_e32 v16, 16, v12
	v_sub_f32_e32 v16, v16, v39
	v_mul_f32_e32 v16, v41, v16
	v_and_b32_e32 v12, 0xffff0000, v12
	s_waitcnt vmcnt(2)
; __device__ __forceinline__ float bflo(unsigned w) { return __uint_as_float(w << 16); }
; __device__ __forceinline__ float bfhi(unsigned w) { return __uint_as_float(w & 0xffff0000u); }
; __device__ void gmlp_item(const Params& p, int layer, int b, int n, int g, char* smem) {
;     ...
; #pragma unroll
;     for (int i = 0; i < 8; ++i) {
;       int q = tid + 256 * i;
;       int st = q & 127, c0 = (q >> 7) * 8;
;       unsigned w[4] = {raw[i].x, raw[i].y, raw[i].z, raw[i].w};
;       float mu = mu_s[st], rs = rs_s[st];
;       const float4* gp = reinterpret_cast<const float4*>(p.gm_gain + (size_t)layer * 512 + g * 128 + c0);
;       float4 g0 = gp[0], g1 = gp[1];
;       float gg[8] = {g0.x, g0.y, g0.z, g0.w, g1.x, g1.y, g1.z, g1.w};
; #pragma unroll
;       for (int e = 0; e < 8; ++e) {
;         float v = (e & 1) ? bfhi(w[e >> 1]) : bflo(w[e >> 1]);
;         float val = (v - mu) * rs * gg[e];
;         *reinterpret_cast<u16*>(smem + 32768 + (st >> 5) * 8192 + (c0 + e) * 64 + (st & 31) * 2) = f2bf(val);
;       }
;     }
;   }
; #pragma unroll 2
;   for (int i = 0; i < 8; ++i) {
;     int q = tid + 256 * i;
;     int t = q >> 4, cch = q & 15;
;     uint4 v = *reinterpret_cast<const uint4*>(Ws + (size_t)g * 16384 + t * 128 + cch * 8);
;     *reinterpret_cast<uint4*>(smem + (cch >> 2) * 8192 + t * 64 + (cch & 3) * 16) = v;
;   }
	v_mul_f32_e32 v16, v16, v70
	v_sub_f32_e32 v12, v12, v39
	v_mul_f32_e32 v12, v41, v12
	v_cvt_pk_bf16_f32 v16, 0, v16
	v_lshl_add_u32 v43, v54, 6, v37
	v_mul_f32_e32 v12, v12, v71
	ds_write_b16_d16_hi v43, v16 offset:32768
	v_cvt_pk_bf16_f32 v12, 0, v12
	ds_write_b16_d16_hi v43, v12 offset:32832
	v_lshlrev_b32_e32 v12, 16, v13
	v_sub_f32_e32 v12, v12, v39
	v_mul_f32_e32 v12, v41, v12
	v_mul_f32_e32 v12, v12, v72
	v_cvt_pk_bf16_f32 v12, 0, v12
	ds_write_b16_d16_hi v43, v12 offset:32896
	v_and_b32_e32 v12, 0xffff0000, v13
	v_sub_f32_e32 v12, v12, v39
	v_mul_f32_e32 v12, v41, v12
	v_mul_f32_e32 v12, v12, v73
	v_cvt_pk_bf16_f32 v12, 0, v12
	ds_write_b16_d16_hi v43, v12 offset:32960
	v_lshlrev_b32_e32 v12, 16, v14
	v_sub_f32_e32 v12, v12, v39
	v_mul_f32_e32 v12, v41, v12
	v_mul_f32_e32 v12, v12, v24
	v_cvt_pk_bf16_f32 v12, 0, v12
	ds_write_b16_d16_hi v43, v12 offset:33024
	v_and_b32_e32 v12, 0xffff0000, v14
	v_sub_f32_e32 v12, v12, v39
	v_mul_f32_e32 v12, v41, v12
	v_mul_f32_e32 v12, v12, v25
	v_cvt_pk_bf16_f32 v12, 0, v12
	ds_write_b16_d16_hi v43, v12 offset:33088
	v_lshlrev_b32_e32 v12, 16, v15
	v_sub_f32_e32 v14, v12, v39
	v_lshl_add_u64 v[12:13], v[50:51], 2, s[6:7]
	global_load_dwordx4 v[16:19], v[12:13], off offset:16
	global_load_dwordx4 v[28:31], v[12:13], off
	v_mul_f32_e32 v12, v41, v14
	v_mul_f32_e32 v12, v12, v26
	v_cvt_pk_bf16_f32 v12, 0, v12
	ds_write_b16_d16_hi v43, v12 offset:33152
	v_and_b32_e32 v12, 0xffff0000, v15
	v_sub_f32_e32 v12, v12, v39
	v_mul_f32_e32 v12, v41, v12
	v_mul_f32_e32 v12, v12, v27
	v_cvt_pk_bf16_f32 v12, 0, v12
	v_lshl_or_b32 v13, v42, 6, v159
	v_add_u32_e32 v13, v37, v13
	ds_write_b16_d16_hi v13, v12 offset:32768
	v_lshlrev_b32_e32 v12, 16, v8
	v_sub_f32_e32 v12, v12, v39
	v_mul_f32_e32 v12, v41, v12
	v_and_b32_e32 v8, 0xffff0000, v8
	s_waitcnt vmcnt(2)
	v_mul_f32_e32 v12, v12, v56
	v_sub_f32_e32 v8, v8, v39
	v_mul_f32_e32 v8, v41, v8
	v_cvt_pk_bf16_f32 v12, 0, v12
	v_lshl_add_u32 v43, v52, 6, v37
	v_mul_f32_e32 v8, v8, v57
	ds_write_b16_d16_hi v43, v12 offset:32768
	v_cvt_pk_bf16_f32 v8, 0, v8
	ds_write_b16_d16_hi v43, v8 offset:32832
	v_lshlrev_b32_e32 v8, 16, v9
	v_sub_f32_e32 v8, v8, v39
	v_mul_f32_e32 v8, v41, v8
	v_mul_f32_e32 v8, v8, v58
	v_cvt_pk_bf16_f32 v8, 0, v8
	ds_write_b16_d16_hi v43, v8 offset:32896
	v_and_b32_e32 v8, 0xffff0000, v9
	v_sub_f32_e32 v8, v8, v39
	v_mul_f32_e32 v8, v41, v8
	v_mul_f32_e32 v8, v8, v59
	v_cvt_pk_bf16_f32 v8, 0, v8
	ds_write_b16_d16_hi v43, v8 offset:32960
	v_lshlrev_b32_e32 v8, 16, v10
	v_sub_f32_e32 v8, v8, v39
	v_mul_f32_e32 v8, v41, v8
	v_mul_f32_e32 v8, v8, v20
	v_cvt_pk_bf16_f32 v8, 0, v8
	ds_write_b16_d16_hi v43, v8 offset:33024
	v_and_b32_e32 v8, 0xffff0000, v10
	v_sub_f32_e32 v8, v8, v39
	v_mul_f32_e32 v8, v41, v8
	v_mul_f32_e32 v8, v8, v21
	v_cvt_pk_bf16_f32 v10, 0, v8
	v_lshl_add_u64 v[8:9], v[32:33], 2, s[6:7]
	global_load_dwordx4 v[12:15], v[8:9], off offset:16
	global_load_dwordx4 v[24:27], v[8:9], off
	v_lshlrev_b32_e32 v8, 16, v11
	v_sub_f32_e32 v8, v8, v39
	v_mul_f32_e32 v8, v41, v8
	v_mul_f32_e32 v8, v8, v22
	v_cvt_pk_bf16_f32 v8, 0, v8
	ds_write_b16_d16_hi v43, v8 offset:33152
	v_and_b32_e32 v8, 0xffff0000, v11
	v_sub_f32_e32 v8, v8, v39
	v_mul_f32_e32 v8, v41, v8
	v_mul_f32_e32 v8, v8, v23
	v_cvt_pk_bf16_f32 v8, 0, v8
	v_lshl_or_b32 v9, v40, 6, v159
	v_add_u32_e32 v9, v37, v9
	ds_write_b16_d16_hi v43, v10 offset:33088
	ds_write_b16_d16_hi v9, v8 offset:32768
	v_lshlrev_b32_e32 v8, 16, v4
	v_sub_f32_e32 v8, v8, v39
	v_mul_f32_e32 v8, v41, v8
	v_and_b32_e32 v4, 0xffff0000, v4
	s_waitcnt vmcnt(2)
	v_mul_f32_e32 v8, v8, v28
	v_sub_f32_e32 v4, v4, v39
	v_mul_f32_e32 v4, v41, v4
	v_cvt_pk_bf16_f32 v8, 0, v8
	v_lshl_add_u32 v9, v50, 6, v37
	v_mul_f32_e32 v4, v4, v29
	ds_write_b16_d16_hi v9, v8 offset:32768
	v_cvt_pk_bf16_f32 v4, 0, v4
	ds_write_b16_d16_hi v9, v4 offset:32832
	v_lshlrev_b32_e32 v4, 16, v5
	v_sub_f32_e32 v4, v4, v39
	v_mul_f32_e32 v4, v41, v4
	v_mul_f32_e32 v4, v4, v30
	v_cvt_pk_bf16_f32 v4, 0, v4
	ds_write_b16_d16_hi v9, v4 offset:32896
	v_and_b32_e32 v4, 0xffff0000, v5
	v_sub_f32_e32 v4, v4, v39
	v_mul_f32_e32 v4, v41, v4
	v_mul_f32_e32 v4, v4, v31
	v_cvt_pk_bf16_f32 v4, 0, v4
	ds_write_b16_d16_hi v9, v4 offset:32960
	v_lshlrev_b32_e32 v4, 16, v6
	v_sub_f32_e32 v4, v4, v39
	v_mul_f32_e32 v4, v41, v4
	v_mul_f32_e32 v4, v4, v16
	v_cvt_pk_bf16_f32 v4, 0, v4
	ds_write_b16_d16_hi v9, v4 offset:33024
	v_and_b32_e32 v4, 0xffff0000, v6
	v_sub_f32_e32 v4, v4, v39
	v_mul_f32_e32 v4, v41, v4
	v_mul_f32_e32 v4, v4, v17
	v_cvt_pk_bf16_f32 v4, 0, v4
	ds_write_b16_d16_hi v9, v4 offset:33088
	v_lshlrev_b32_e32 v4, 16, v7
	v_sub_f32_e32 v4, v4, v39
	v_mul_f32_e32 v4, v41, v4
	v_mul_f32_e32 v4, v4, v18
	v_cvt_pk_bf16_f32 v4, 0, v4
	ds_write_b16_d16_hi v9, v4 offset:33152
	v_and_b32_e32 v4, 0xffff0000, v7
	v_sub_f32_e32 v4, v4, v39
	v_mul_f32_e32 v4, v41, v4
	v_mul_f32_e32 v4, v4, v19
	v_cvt_pk_bf16_f32 v4, 0, v4
	v_lshl_or_b32 v5, v38, 6, v159
	v_add_u32_e32 v5, v37, v5
	ds_write_b16_d16_hi v5, v4 offset:32768
	v_lshlrev_b32_e32 v4, 16, v0
	v_sub_f32_e32 v4, v4, v39
	v_mul_f32_e32 v4, v41, v4
	v_and_b32_e32 v0, 0xffff0000, v0
	s_waitcnt vmcnt(0)
	v_mul_f32_e32 v4, v4, v24
	v_sub_f32_e32 v0, v0, v39
	v_mul_f32_e32 v0, v41, v0
	v_cvt_pk_bf16_f32 v4, 0, v4
	v_lshl_add_u32 v5, v32, 6, v37
	v_mul_f32_e32 v0, v0, v25
	ds_write_b16_d16_hi v5, v4 offset:32768
	v_cvt_pk_bf16_f32 v0, 0, v0
	ds_write_b16_d16_hi v5, v0 offset:32832
	v_lshlrev_b32_e32 v0, 16, v1
	v_sub_f32_e32 v0, v0, v39
	v_mul_f32_e32 v0, v41, v0
	v_mul_f32_e32 v0, v0, v26
	v_cvt_pk_bf16_f32 v0, 0, v0
	ds_write_b16_d16_hi v5, v0 offset:32896
	v_and_b32_e32 v0, 0xffff0000, v1
	v_sub_f32_e32 v0, v0, v39
	v_mul_f32_e32 v0, v41, v0
	v_mul_f32_e32 v0, v0, v27
	v_cvt_pk_bf16_f32 v0, 0, v0
	ds_write_b16_d16_hi v5, v0 offset:32960
	v_lshlrev_b32_e32 v0, 16, v2
	v_sub_f32_e32 v0, v0, v39
	v_mul_f32_e32 v0, v41, v0
	v_mul_f32_e32 v0, v0, v12
	v_cvt_pk_bf16_f32 v0, 0, v0
	ds_write_b16_d16_hi v5, v0 offset:33024
	v_and_b32_e32 v0, 0xffff0000, v2
	v_sub_f32_e32 v0, v0, v39
	v_mul_f32_e32 v0, v41, v0
	v_mul_f32_e32 v0, v0, v13
	v_cvt_pk_bf16_f32 v0, 0, v0
	ds_write_b16_d16_hi v5, v0 offset:33088
	v_lshlrev_b32_e32 v0, 16, v3
	v_sub_f32_e32 v0, v0, v39
	v_mul_f32_e32 v0, v41, v0
	v_mul_f32_e32 v0, v0, v14
	v_cvt_pk_bf16_f32 v0, 0, v0
	ds_write_b16_d16_hi v5, v0 offset:33152
	v_and_b32_e32 v0, 0xffff0000, v3
	v_sub_f32_e32 v0, v0, v39
	v_mul_f32_e32 v0, v41, v0
	v_mul_f32_e32 v0, v0, v15
	s_lshl_b32 s6, s10, 15
	v_cvt_pk_bf16_f32 v0, 0, v0
	v_lshl_or_b32 v1, v36, 6, v159
	s_add_u32 s6, s11, s6
	v_add_u32_e32 v1, v37, v1
	s_addc_u32 s7, s48, 0
	v_lshlrev_b32_e32 v3, 4, v60
	ds_write_b16_d16_hi v1, v0 offset:32768
	v_lshl_add_u64 v[0:1], s[6:7], 0, v[128:129]
	v_lshlrev_b32_e32 v2, 11, v60
	v_and_b32_e32 v3, 48, v3
	v_lshl_add_u64 v[0:1], v[0:1], 0, s[38:39]
	v_and_or_b32 v2, v2, s65, v3
	s_mov_b32 s6, 0
; #define MFMA16(a, b, c) __builtin_amdgcn_mfma_f32_16x16x32_bf16(a, b, c, 0, 0, 0)
; __device__ void gmlp_item(const Params& p, int layer, int b, int n, int g, char* smem) {
;     ...
; #pragma unroll 2
;   for (int i = 0; i < 8; ++i) {
;     int q = tid + 256 * i;
;     int t = q >> 4, cch = q & 15;
;     uint4 v = *reinterpret_cast<const uint4*>(Ws + (size_t)g * 16384 + t * 128 + cch * 8);
;     *reinterpret_cast<uint4*>(smem + (cch >> 2) * 8192 + t * 64 + (cch & 3) * 16) = v;
;   }
;   __syncthreads();
;   f32x4 acc[4][4];
; #pragma unroll
;   for (int m = 0; m < 4; ++m)
; #pragma unroll
;     for (int nn = 0; nn < 4; ++nn) acc[m][nn] = f32x4{0.f, 0.f, 0.f, 0.f};
; #pragma unroll
;   for (int ks = 0; ks < 4; ++ks) {
;     bf16x8 a[4], bb[4];
; #pragma unroll
;     for (int m = 0; m < 4; ++m)
;       a[m] = *reinterpret_cast<const bf16x8*>(smem + ks * 8192 + (wr * 64 + m * 16 + fr) * 64 + fq * 16);
; #pragma unroll
;     for (int nn = 0; nn < 4; ++nn)
;       bb[nn] = *reinterpret_cast<const bf16x8*>(smem + 32768 + ks * 8192 + (wc * 64 + nn * 16 + fr) * 64 + fq * 16);
; #pragma unroll
;     for (int m = 0; m < 4; ++m)
; #pragma unroll
;       for (int nn = 0; nn < 4; ++nn) acc[m][nn] = MFMA16(a[m], bb[nn], acc[m][nn]);
;   }
.LBB0_159:
	v_add_u32_e32 v3, s6, v60
	v_ashrrev_i32_e32 v12, 4, v3
	v_add_u32_e32 v3, 0x100, v3
	v_ashrrev_i32_e32 v3, 4, v3
	v_lshlrev_b32_e32 v4, 7, v12
	v_lshlrev_b32_e32 v6, 7, v3
	v_ashrrev_i32_e32 v5, 31, v4
	v_ashrrev_i32_e32 v7, 31, v6
	v_lshl_add_u64 v[4:5], v[4:5], 1, v[0:1]
	v_lshl_add_u64 v[8:9], v[6:7], 1, v[0:1]
	global_load_dwordx4 v[4:7], v[4:5], off
	s_nop 0
	global_load_dwordx4 v[8:11], v[8:9], off
	s_addk_i32 s6, 0x200
	s_cmpk_lg_i32 s6, 0x800
	v_lshl_add_u32 v12, v12, 6, v2
	v_lshl_add_u32 v3, v3, 6, v2
	s_waitcnt vmcnt(1)
	ds_write_b128 v12, v[4:7]
	s_waitcnt vmcnt(0)
	ds_write_b128 v3, v[8:11]
	s_cbranch_scc1 .LBB0_159
	v_bfe_u32 v32, v60, 4, 2
	v_ashrrev_i32_e32 v33, 7, v60
	v_lshlrev_b32_e32 v4, 4, v32
	v_lshlrev_b32_e32 v0, 12, v33
	v_lshlrev_b32_e32 v5, 6, v35
	v_or3_b32 v37, v4, v0, v5
	s_waitcnt lgkmcnt(0)
	s_barrier
	ds_read_b128 v[0:3], v37
	v_bfe_u32 v39, v60, 6, 1
	v_lshlrev_b32_e32 v6, 12, v39
	v_or3_b32 v41, v4, v6, v5
	ds_read_b128 v[4:7], v41 offset:32768
	ds_read_b128 v[8:11], v37 offset:1024
	ds_read_b128 v[12:15], v41 offset:33792
	ds_read_b128 v[24:27], v41 offset:34816
	ds_read_b128 v[28:31], v41 offset:35840
	s_waitcnt lgkmcnt(4)
	v_mfma_f32_16x16x32_bf16 v[16:19], v[0:3], v[4:7], 0
	s_ashr_i32 s7, s9, 31
	s_add_u32 s6, s28, s9
	s_addc_u32 s7, s29, s7
	s_waitcnt lgkmcnt(2)
	v_mfma_f32_16x16x32_bf16 v[20:23], v[0:3], v[12:15], 0
	v_lshlrev_b32_e32 v33, 6, v33
	s_lshl_b32 s9, s8, 2
	v_lshl_or_b32 v32, v32, 2, v33
	s_waitcnt lgkmcnt(1)
	v_mfma_f32_16x16x32_bf16 v[50:53], v[0:3], v[24:27], 0
	s_add_u32 s10, s12, s9
	s_addc_u32 s11, s13, 0
	v_ashrrev_i32_e32 v33, 31, v32
	s_waitcnt lgkmcnt(0)
	v_mfma_f32_16x16x32_bf16 v[54:57], v[0:3], v[28:31], 0
	ds_read_b128 v[0:3], v37 offset:2048
	ds_read_b128 v[74:77], v37 offset:3072
	ds_read_b128 v[98:101], v37 offset:8192
	v_lshl_add_u64 v[58:59], v[32:33], 2, s[10:11]
	v_mfma_f32_16x16x32_bf16 v[62:65], v[8:11], v[4:7], 0
	v_lshlrev_b32_e32 v33, 2, v35
	v_lshl_or_b32 v126, v39, 8, v33
	v_mad_u64_u32 v[32:33], s[10:11], v32, s67, v[126:127]
	v_mfma_f32_16x16x32_bf16 v[66:69], v[8:11], v[12:15], 0
	v_add_u32_e32 v33, 0x400, v32
	v_ashrrev_i32_e32 v49, 31, v48
	v_ashrrev_i32_e32 v47, 31, v46
	v_mfma_f32_16x16x32_bf16 v[70:73], v[8:11], v[24:27], 0
	v_ashrrev_i32_e32 v45, 31, v44
	v_ashrrev_i32_e32 v43, 31, v42
	v_ashrrev_i32_e32 v39, 31, v38
	v_mfma_f32_16x16x32_bf16 v[8:11], v[8:11], v[28:31], 0
	s_waitcnt lgkmcnt(2)
	v_mfma_f32_16x16x32_bf16 v[78:81], v[0:3], v[4:7], 0
	v_mfma_f32_16x16x32_bf16 v[82:85], v[0:3], v[12:15], 0
	v_mfma_f32_16x16x32_bf16 v[86:89], v[0:3], v[24:27], 0
	v_mfma_f32_16x16x32_bf16 v[90:93], v[0:3], v[28:31], 0
	s_waitcnt lgkmcnt(1)
	v_mfma_f32_16x16x32_bf16 v[94:97], v[74:77], v[4:7], 0
	v_mfma_f32_16x16x32_bf16 v[12:15], v[74:77], v[12:15], 0
	v_mfma_f32_16x16x32_bf16 v[24:27], v[74:77], v[24:27], 0
	v_mfma_f32_16x16x32_bf16 v[0:3], v[74:77], v[28:31], 0
	ds_read_b128 v[28:31], v41 offset:40960
	ds_read_b128 v[74:77], v37 offset:9216
	ds_read_b128 v[102:105], v41 offset:41984
	ds_read_b128 v[106:109], v41 offset:43008
	ds_read_b128 v[4:7], v41 offset:44032
	s_waitcnt lgkmcnt(4)
	v_mfma_f32_16x16x32_bf16 v[16:19], v[98:101], v[28:31], v[16:19]
	s_waitcnt lgkmcnt(2)
	v_mfma_f32_16x16x32_bf16 v[20:23], v[98:101], v[102:105], v[20:23]
	s_waitcnt lgkmcnt(1)
	v_mfma_f32_16x16x32_bf16 v[50:53], v[98:101], v[106:109], v[50:53]
	s_waitcnt lgkmcnt(0)
	v_mfma_f32_16x16x32_bf16 v[54:57], v[98:101], v[4:7], v[54:57]
	ds_read_b128 v[98:101], v37 offset:10240
	v_mfma_f32_16x16x32_bf16 v[62:65], v[74:77], v[28:31], v[62:65]
	v_mfma_f32_16x16x32_bf16 v[66:69], v[74:77], v[102:105], v[66:69]
	v_mfma_f32_16x16x32_bf16 v[70:73], v[74:77], v[106:109], v[70:73]
	v_mfma_f32_16x16x32_bf16 v[8:11], v[74:77], v[4:7], v[8:11]
	ds_read_b128 v[74:77], v37 offset:11264
	ds_read_b128 v[110:113], v37 offset:16384
	ds_read_b128 v[114:117], v37 offset:17408
	ds_read_b128 v[118:121], v37 offset:18432
	ds_read_b128 v[122:125], v37 offset:19456
	ds_read_b128 v[134:137], v41 offset:49152
	ds_read_b128 v[138:141], v41 offset:50176
	ds_read_b128 v[146:149], v41 offset:51200
	ds_read_b128 v[150:153], v41 offset:52224
	ds_read_b128 v[162:165], v37 offset:24576
	ds_read_b128 v[166:169], v37 offset:25600
	s_waitcnt lgkmcnt(11)
	v_mfma_f32_16x16x32_bf16 v[78:81], v[98:101], v[28:31], v[78:81]
	v_mfma_f32_16x16x32_bf16 v[82:85], v[98:101], v[102:105], v[82:85]
	v_mfma_f32_16x16x32_bf16 v[86:89], v[98:101], v[106:109], v[86:89]
	v_mfma_f32_16x16x32_bf16 v[90:93], v[98:101], v[4:7], v[90:93]
	ds_read_b128 v[98:101], v37 offset:26624
	ds_read_b128 v[170:173], v37 offset:27648
	ds_read_b128 v[174:177], v41 offset:57344
	ds_read_b128 v[178:181], v41 offset:58368
	s_waitcnt lgkmcnt(14)
	v_mfma_f32_16x16x32_bf16 v[28:31], v[74:77], v[28:31], v[94:97]
	s_nop 2
	ds_read_b128 v[94:97], v41 offset:59392
	ds_read_b128 v[182:185], v41 offset:60416
	s_waitcnt lgkmcnt(0)
	s_barrier
; #define MFMA16(a, b, c) __builtin_amdgcn_mfma_f32_16x16x32_bf16(a, b, c, 0, 0, 0)
; __device__ void gmlp_item(const Params& p, int layer, int b, int n, int g, char* smem) {
;     ...
; #pragma unroll
;     for (int m = 0; m < 4; ++m)
; #pragma unroll
;       for (int nn = 0; nn < 4; ++nn) acc[m][nn] = MFMA16(a[m], bb[nn], acc[m][nn]);
;   }
;   __syncthreads();
;   {
;     float* Tf = reinterpret_cast<float*>(smem);
; #pragma unroll
;     for (int m = 0; m < 4; ++m)
; #pragma unroll
;       for (int j = 0; j < 4; ++j) {
;         int t = wr * 64 + m * 16 + fq * 4 + j;
;         float bias = p.gm_b_s[(size_t)layer * 512 + g * 128 + t];
; #pragma unroll
;         for (int nn = 0; nn < 4; ++nn) Tf[t * 132 + wc * 64 + nn * 16 + fr] = acc[m][nn][j] + bias;
;       }
	v_mfma_f32_16x16x32_bf16 v[16:19], v[110:113], v[134:137], v[16:19]
	global_load_dwordx4 v[186:189], v[58:59], off offset:64
	global_load_dwordx4 v[190:193], v[58:59], off offset:128
	v_mfma_f32_16x16x32_bf16 v[20:23], v[110:113], v[138:141], v[20:23]
	v_ashrrev_i32_e32 v41, 31, v40
	v_mfma_f32_16x16x32_bf16 v[50:53], v[110:113], v[146:149], v[50:53]
	v_mfma_f32_16x16x32_bf16 v[54:57], v[110:113], v[150:153], v[54:57]
	global_load_dwordx4 v[110:113], v[58:59], off
	v_mfma_f32_16x16x32_bf16 v[16:19], v[162:165], v[174:177], v[16:19]
	v_mfma_f32_16x16x32_bf16 v[20:23], v[162:165], v[178:181], v[20:23]
	v_mfma_f32_16x16x32_bf16 v[50:53], v[162:165], v[94:97], v[50:53]
	s_waitcnt vmcnt(0)
	s_nop 4
	v_add_f32_e32 v16, v16, v110
	v_mfma_f32_16x16x32_bf16 v[54:57], v[162:165], v[182:185], v[54:57]
	v_add_f32_e32 v20, v20, v110
	ds_write2_b32 v32, v16, v20 offset1:16
	v_add_f32_e32 v16, v50, v110
	v_add_f32_e32 v35, v53, v113
	v_mfma_f32_16x16x32_bf16 v[62:65], v[114:117], v[134:137], v[62:65]
	s_nop 2
	v_add_f32_e32 v20, v54, v110
	ds_write2_b32 v32, v16, v20 offset0:32 offset1:48
	v_add_f32_e32 v16, v17, v111
	v_add_f32_e32 v17, v21, v111
	ds_write2_b32 v32, v16, v17 offset0:132 offset1:148
	v_add_f32_e32 v16, v51, v111
	v_add_f32_e32 v17, v55, v111
	ds_write2_b32 v32, v16, v17 offset0:164 offset1:180
	v_add_f32_e32 v16, v18, v112
	v_add_f32_e32 v17, v22, v112
	ds_write2_b32 v33, v16, v17 offset0:8 offset1:24
	v_add_f32_e32 v16, v52, v112
	global_load_dwordx4 v[50:53], v[58:59], off offset:192
	v_mfma_f32_16x16x32_bf16 v[66:69], v[114:117], v[138:141], v[66:69]
	v_add_f32_e32 v17, v56, v112
	v_add_f32_e32 v20, v19, v113
	v_add_f32_e32 v21, v23, v113
	v_mfma_f32_16x16x32_bf16 v[70:73], v[114:117], v[146:149], v[70:73]
	ds_write2_b32 v33, v16, v17 offset0:40 offset1:56
	ds_write2_b32 v33, v20, v21 offset0:140 offset1:156
	v_add_f32_e32 v37, v57, v113
	v_mfma_f32_16x16x32_bf16 v[8:11], v[114:117], v[150:153], v[8:11]
	ds_write2_b32 v33, v35, v37 offset0:172 offset1:188
	v_add_u32_e32 v33, 0x2000, v32
	v_ashrrev_i32_e32 v35, 31, v34
	v_mfma_f32_16x16x32_bf16 v[16:19], v[166:169], v[174:177], v[62:65]
	v_ashrrev_i32_e32 v37, 31, v36
	v_lshl_add_u64 v[58:59], v[42:43], 0, s[26:27]
	v_mfma_f32_16x16x32_bf16 v[20:23], v[166:169], v[178:181], v[66:69]
	v_mfma_f32_16x16x32_bf16 v[54:57], v[166:169], v[94:97], v[70:73]
	s_nop 3
	v_add_f32_e32 v16, v16, v186
	s_nop 1
	v_add_f32_e32 v20, v20, v186
	ds_write2_b32 v33, v16, v20 offset0:64 offset1:80
	v_mfma_f32_16x16x32_bf16 v[8:11], v[166:169], v[182:185], v[8:11]
	v_add_u32_e32 v20, 0x2400, v32
	v_add_f32_e32 v16, v54, v186
	v_mfma_f32_16x16x32_bf16 v[62:65], v[118:121], v[134:137], v[78:81]
	v_mfma_f32_16x16x32_bf16 v[66:69], v[118:121], v[138:141], v[82:85]
	s_nop 3
	v_add_f32_e32 v8, v8, v186
	ds_write2_b32 v33, v16, v8 offset0:96 offset1:112
	v_add_f32_e32 v8, v17, v187
	v_add_f32_e32 v16, v21, v187
	ds_write2_b32 v33, v8, v16 offset0:196 offset1:212
	v_add_f32_e32 v8, v55, v187
	v_add_f32_e32 v9, v9, v187
	ds_write2_b32 v33, v8, v9 offset0:228 offset1:244
	v_add_f32_e32 v8, v18, v188
	v_add_f32_e32 v9, v22, v188
	v_mfma_f32_16x16x32_bf16 v[70:73], v[118:121], v[146:149], v[86:89]
	ds_write2_b32 v20, v8, v9 offset0:72 offset1:88
	v_add_f32_e32 v8, v56, v188
	v_add_f32_e32 v9, v10, v188
	v_mfma_f32_16x16x32_bf16 v[78:81], v[118:121], v[150:153], v[90:93]
	ds_write2_b32 v20, v8, v9 offset0:104 offset1:120
	v_add_f32_e32 v8, v19, v189
	v_add_f32_e32 v9, v23, v189
	v_mfma_f32_16x16x32_bf16 v[16:19], v[98:101], v[174:177], v[62:65]
	ds_write2_b32 v20, v8, v9 offset0:204 offset1:220
	v_add_f32_e32 v21, v57, v189
	v_add_f32_e32 v22, v11, v189
	v_mfma_f32_16x16x32_bf16 v[8:11], v[98:101], v[178:181], v[66:69]
	ds_write2_b32 v20, v21, v22 offset0:236 offset1:252
	s_nop 2
	v_add_f32_e32 v16, v16, v190
	v_add_u32_e32 v33, 0x4000, v32
	v_mfma_f32_16x16x32_bf16 v[20:23], v[98:101], v[94:97], v[70:73]
	v_lshl_add_u64 v[62:63], v[38:39], 0, s[26:27]
	v_add_f32_e32 v8, v8, v190
	ds_write2_b32 v33, v16, v8 offset0:128 offset1:144
	v_mfma_f32_16x16x32_bf16 v[54:57], v[98:101], v[182:185], v[78:81]
	v_add_f32_e32 v10, v10, v192
	s_nop 2
	v_add_f32_e32 v8, v20, v190
	v_mfma_f32_16x16x32_bf16 v[12:15], v[74:77], v[102:105], v[12:15]
	v_mfma_f32_16x16x32_bf16 v[24:27], v[74:77], v[106:109], v[24:27]
	s_nop 0
	v_add_f32_e32 v16, v54, v190
	ds_write2_b32 v33, v8, v16 offset0:160 offset1:176
	v_add_f32_e32 v8, v17, v191
	v_mfma_f32_16x16x32_bf16 v[0:3], v[74:77], v[4:7], v[0:3]
	v_add_f32_e32 v4, v9, v191
	v_add_u32_e32 v9, 0x4400, v32
	ds_write2_b32 v9, v8, v4 offset0:4 offset1:20
	v_mfma_f32_16x16x32_bf16 v[4:7], v[122:125], v[134:137], v[28:31]
	v_add_f32_e32 v8, v21, v191
	v_add_f32_e32 v16, v55, v191
	ds_write2_b32 v9, v8, v16 offset0:36 offset1:52
	v_mfma_f32_16x16x32_bf16 v[12:15], v[122:125], v[138:141], v[12:15]
	v_add_f32_e32 v8, v18, v192
	ds_write2_b32 v9, v8, v10 offset0:136 offset1:152
	v_add_f32_e32 v8, v22, v192
	v_mfma_f32_16x16x32_bf16 v[24:27], v[122:125], v[146:149], v[24:27]
	v_add_f32_e32 v10, v56, v192
	ds_write2_b32 v9, v8, v10 offset0:168 offset1:184
	v_add_f32_e32 v8, v19, v193
	v_mfma_f32_16x16x32_bf16 v[0:3], v[122:125], v[150:153], v[0:3]
	v_add_f32_e32 v9, v11, v193
	v_add_u32_e32 v16, 0x4800, v32
	ds_write2_b32 v16, v8, v9 offset0:12 offset1:28
	v_mfma_f32_16x16x32_bf16 v[4:7], v[170:173], v[174:177], v[4:7]
	v_add_f32_e32 v17, v23, v193
	v_add_f32_e32 v18, v57, v193
	ds_write2_b32 v16, v17, v18 offset0:44 offset1:60
	v_mfma_f32_16x16x32_bf16 v[8:11], v[170:173], v[178:181], v[12:15]
	v_add_u32_e32 v16, 0x6000, v32
	s_waitcnt vmcnt(0)
; __device__ __forceinline__ unsigned pack2(float a, float b) { return (unsigned)f2bf(a) | ((unsigned)f2bf(b) << 16); }
; __device__ __forceinline__ float bflo(unsigned w) { return __uint_as_float(w << 16); }
; __device__ __forceinline__ float bfhi(unsigned w) { return __uint_as_float(w & 0xffff0000u); }
; __device__ __forceinline__ float silu_f(float g) { return g / (1.f + __expf(-g)); }
; __device__ void gmlp_item(const Params& p, int layer, int b, int n, int g, char* smem) {
;     ...
;     __syncthreads();
;     uint4 uu[8], gt[8];
; #pragma unroll
;     for (int i = 0; i < 8; ++i) {
;       int q = tid + 256 * i, t = q >> 4, c = (q & 15) * 8;
;       uu[i] = *reinterpret_cast<const uint4*>(P + (t0 + t) * NP + g * 128 + c);
;       gt[i] = *reinterpret_cast<const uint4*>(P + (t0 + t) * NP + 1024 + g * 128 + c);
;     }
; #pragma unroll
;     for (int i = 0; i < 8; ++i) {
;       int q = tid + 256 * i, t = q >> 4, c = (q & 15) * 8;
;       float4 m0 = *reinterpret_cast<const float4*>(Tf + t * 132 + c);
;       float4 m1 = *reinterpret_cast<const float4*>(Tf + t * 132 + c + 4);
;       float mm[8] = {m0.x, m0.y, m0.z, m0.w, m1.x, m1.y, m1.z, m1.w};
;       unsigned uw[4] = {uu[i].x, uu[i].y, uu[i].z, uu[i].w};
;       unsigned gw[4] = {gt[i].x, gt[i].y, gt[i].z, gt[i].w};
;       unsigned ow[4];
; #pragma unroll
;       for (int e = 0; e < 4; ++e) {
;         float y0 = bflo(uw[e]) * mm[2 * e] * silu_f(bflo(gw[e]));
;         float y1 = bfhi(uw[e]) * mm[2 * e + 1] * silu_f(bfhi(gw[e]));
;         ow[e] = pack2(y0, y1);
;       }
;       *reinterpret_cast<uint4*>(Y + (t0 + t) * YW + g * 128 + c) = make_uint4(ow[0], ow[1], ow[2], ow[3]);
	s_nop 1
	v_add_f32_e32 v4, v4, v50
	v_lshl_add_u64 v[56:57], v[36:37], 0, s[26:27]
	v_mfma_f32_16x16x32_bf16 v[12:15], v[170:173], v[94:97], v[24:27]
	v_lshl_add_u64 v[20:21], v[44:45], 0, s[26:27]
	v_add_f32_e32 v8, v8, v50
	ds_write2_b32 v16, v4, v8 offset0:192 offset1:208
	v_mfma_f32_16x16x32_bf16 v[0:3], v[170:173], v[182:185], v[0:3]
	s_nop 3
	v_add_f32_e32 v4, v12, v50
	s_nop 2
	v_add_f32_e32 v0, v0, v50
	ds_write2_b32 v16, v4, v0 offset0:224 offset1:240
	v_add_f32_e32 v0, v5, v51
	v_add_f32_e32 v4, v9, v51
	v_add_u32_e32 v5, 0x6400, v32
	ds_write2_b32 v5, v0, v4 offset0:68 offset1:84
	v_add_f32_e32 v0, v13, v51
	v_add_f32_e32 v1, v1, v51
	ds_write2_b32 v5, v0, v1 offset0:100 offset1:116
	v_add_f32_e32 v0, v6, v52
	v_add_f32_e32 v1, v10, v52
	ds_write2_b32 v5, v0, v1 offset0:200 offset1:216
	v_add_f32_e32 v0, v14, v52
	v_add_f32_e32 v1, v2, v52
	ds_write2_b32 v5, v0, v1 offset0:232 offset1:248
	v_add_f32_e32 v0, v7, v53
	v_add_f32_e32 v1, v11, v53
	v_add_u32_e32 v2, 0x6800, v32
	ds_write2_b32 v2, v0, v1 offset0:76 offset1:92
	v_add_f32_e32 v0, v15, v53
	v_add_f32_e32 v1, v3, v53
	ds_write2_b32 v2, v0, v1 offset0:108 offset1:124
	v_lshlrev_b32_e32 v0, 3, v60
	v_lshl_add_u64 v[8:9], v[34:35], 0, s[26:27]
	v_mov_b64_e32 v[10:11], s[4:5]
	v_and_b32_e32 v24, 0x78, v0
	v_mad_u64_u32 v[0:1], s[4:5], v8, s55, v[10:11]
	v_mad_i32_i24 v1, v9, s55, v1
	s_lshl_b32 s4, s8, 1
	s_mov_b32 s5, s27
	v_lshl_add_u64 v[0:1], v[0:1], 0, s[4:5]
	v_lshlrev_b32_e32 v128, 1, v24
	v_lshl_add_u64 v[12:13], v[48:49], 0, s[26:27]
	v_lshl_add_u64 v[52:53], v[0:1], 0, v[128:129]
	v_mad_u64_u32 v[0:1], s[8:9], v12, s55, v[10:11]
	v_mad_i32_i24 v1, v13, s55, v1
	v_lshl_add_u64 v[0:1], v[0:1], 0, s[4:5]
	v_lshl_add_u64 v[32:33], v[0:1], 0, v[128:129]
	v_mad_u64_u32 v[0:1], s[8:9], v56, s55, v[10:11]
	v_mad_i32_i24 v1, v57, s55, v1
	v_lshl_add_u64 v[0:1], v[0:1], 0, s[4:5]
	v_lshl_add_u64 v[4:5], v[0:1], 0, v[128:129]
	s_waitcnt lgkmcnt(0)
	s_barrier
	global_load_dwordx4 v[0:3], v[4:5], off
	s_nop 0
	global_load_dwordx4 v[4:7], v[4:5], off offset:2048
	v_lshl_add_u64 v[16:17], v[46:47], 0, s[26:27]
	v_mad_u64_u32 v[14:15], s[8:9], v16, s55, v[10:11]
	v_mad_i32_i24 v15, v17, s55, v15
	v_lshl_add_u64 v[14:15], v[14:15], 0, s[4:5]
	v_lshl_add_u64 v[30:31], v[14:15], 0, v[128:129]
	v_mad_u64_u32 v[14:15], s[8:9], v20, s55, v[10:11]
	v_mad_i32_i24 v15, v21, s55, v15
	v_lshl_add_u64 v[14:15], v[14:15], 0, s[4:5]
	v_lshl_add_u64 v[26:27], v[14:15], 0, v[128:129]
	v_mad_u64_u32 v[14:15], s[8:9], v58, s55, v[10:11]
	v_mad_i32_i24 v15, v59, s55, v15
	v_lshl_add_u64 v[14:15], v[14:15], 0, s[4:5]
	v_lshl_add_u64 v[60:61], v[40:41], 0, s[26:27]
	v_lshl_add_u64 v[22:23], v[14:15], 0, v[128:129]
	v_mad_u64_u32 v[14:15], s[8:9], v60, s55, v[10:11]
	v_mad_u64_u32 v[10:11], s[8:9], v62, s55, v[10:11]
	v_mad_i32_i24 v15, v61, s55, v15
	v_mad_i32_i24 v11, v63, s55, v11
	v_lshl_add_u64 v[14:15], v[14:15], 0, s[4:5]
	v_lshl_add_u64 v[10:11], v[10:11], 0, s[4:5]
	s_add_u32 s4, s6, s4
	s_addc_u32 s5, s7, 0
	v_lshl_add_u64 v[18:19], v[14:15], 0, v[128:129]
	v_lshl_add_u64 v[14:15], v[10:11], 0, v[128:129]
	v_lshlrev_b32_e32 v10, 2, v24
	v_lshl_add_u64 v[24:25], s[4:5], 0, v[128:129]
	v_lshl_add_u64 v[64:65], v[24:25], 0, s[40:41]
	v_mad_u64_u32 v[54:55], s[4:5], v34, s67, v[10:11]
	v_mad_u64_u32 v[34:35], s[4:5], v48, s67, v[10:11]
	v_mad_u64_u32 v[48:49], s[4:5], v12, s68, v[64:65]
	v_mad_u64_u32 v[28:29], s[4:5], v46, s67, v[10:11]
	v_mad_u64_u32 v[46:47], s[4:5], v16, s68, v[64:65]
	v_mad_u64_u32 v[50:51], s[4:5], v8, s68, v[64:65]
	v_mad_i32_i24 v49, v13, s68, v49
	v_mad_i32_i24 v47, v17, s68, v47
	v_mad_u64_u32 v[24:25], s[4:5], v44, s67, v[10:11]
	v_mad_u64_u32 v[44:45], s[4:5], v20, s68, v[64:65]
	v_mad_u64_u32 v[16:17], s[4:5], v40, s67, v[10:11]
	v_mad_u64_u32 v[12:13], s[4:5], v38, s67, v[10:11]
	v_mad_i32_i24 v51, v9, s68, v51
	v_mad_i32_i24 v45, v21, s68, v45
	v_mad_u64_u32 v[20:21], s[4:5], v42, s67, v[10:11]
	v_mad_u64_u32 v[8:9], s[4:5], v36, s67, v[10:11]
	v_mad_u64_u32 v[40:41], s[4:5], v60, s68, v[64:65]
	v_mad_i32_i24 v41, v61, s68, v41
	v_mad_u64_u32 v[42:43], s[4:5], v58, s68, v[64:65]
	v_mad_u64_u32 v[36:37], s[4:5], v56, s68, v[64:65]
	v_mad_i32_i24 v43, v59, s68, v43
	v_mad_i32_i24 v37, v57, s68, v37
	v_mad_u64_u32 v[38:39], s[4:5], v62, s68, v[64:65]
	v_mad_i32_i24 v39, v63, s68, v39
	s_waitcnt vmcnt(1)
	v_lshlrev_b32_e32 v63, 16, v1
	s_waitcnt vmcnt(0)
	v_lshlrev_b32_e32 v13, 16, v5
	v_lshlrev_b32_e32 v17, 16, v4
	v_mul_f32_e32 v9, 0xbfb8aa3b, v17
	v_and_b32_e32 v21, 0xffff0000, v5
	v_mul_f32_e32 v5, 0xbfb8aa3b, v13
	v_exp_f32_e32 v60, v9
	v_exp_f32_e32 v61, v5
	ds_read_b128 v[56:59], v8
	ds_read_b128 v[8:11], v8 offset:16
	v_and_b32_e32 v25, 0xffff0000, v4
	v_mul_f32_e32 v4, 0xbfb8aa3b, v25
	v_pk_add_f32 v[60:61], v[60:61], 1.0 op_sel_hi:[1,0]
	s_waitcnt lgkmcnt(1)
	v_mov_b32_e32 v64, v56
	v_exp_f32_e32 v4, v4
	v_lshlrev_b32_e32 v62, 16, v0
	v_mov_b32_e32 v65, v58
	v_rcp_f32_e32 v61, v61
	s_nop 0
	v_mul_f32_e32 v61, v13, v61
	v_and_b32_e32 v1, 0xffff0000, v1
	v_mul_f32_e32 v5, 0xbfb8aa3b, v21
	v_exp_f32_e32 v5, v5
	v_rcp_f32_e32 v60, v60
	s_nop 0
	v_mul_f32_e32 v60, v17, v60
	v_and_b32_e32 v0, 0xffff0000, v0
	v_mov_b32_e32 v58, v57
	v_pk_add_f32 v[4:5], v[4:5], 1.0 op_sel_hi:[1,0]
	v_pk_mul_f32 v[0:1], v[58:59], v[0:1]
	v_pk_mul_f32 v[62:63], v[64:65], v[62:63]
	v_rcp_f32_e32 v5, v5
	s_nop 0
	v_mul_f32_e32 v5, v21, v5
	v_pk_mul_f32 v[60:61], v[60:61], v[62:63]
	v_rcp_f32_e32 v4, v4
	s_nop 0
	v_mul_f32_e32 v4, v25, v4
	v_pk_mul_f32 v[0:1], v[4:5], v[0:1]
	v_cvt_pk_bf16_f32 v1, 0, v1
	v_cvt_pk_bf16_f32 v0, 0, v0
	v_cvt_pk_bf16_f32 v5, 0, v60
	v_cvt_pk_bf16_f32 v4, 0, v61
	v_and_b32_e32 v1, 0xffff0000, v1
	v_and_b32_e32 v0, 0xffff0000, v0
	v_lshlrev_b32_e32 v13, 16, v7
	v_lshlrev_b32_e32 v17, 16, v6
	v_or_b32_sdwa v1, v1, v4 dst_sel:DWORD dst_unused:UNUSED_PAD src0_sel:DWORD src1_sel:WORD_1
	v_or_b32_sdwa v0, v0, v5 dst_sel:DWORD dst_unused:UNUSED_PAD src0_sel:DWORD src1_sel:WORD_1
	v_mul_f32_e32 v4, 0xbfb8aa3b, v17
	v_mul_f32_e32 v5, 0xbfb8aa3b, v13
	v_exp_f32_e32 v4, v4
	v_exp_f32_e32 v5, v5
	v_and_b32_e32 v25, 0xffff0000, v6
	v_mul_f32_e32 v6, 0xbfb8aa3b, v25
	v_and_b32_e32 v21, 0xffff0000, v7
	v_exp_f32_e32 v60, v6
	v_pk_add_f32 v[64:65], v[4:5], 1.0 op_sel_hi:[1,0]
	global_load_dwordx4 v[4:7], v[14:15], off
	global_load_dwordx4 v[56:59], v[14:15], off offset:2048
	s_waitcnt lgkmcnt(0)
; __device__ __forceinline__ unsigned pack2(float a, float b) { return (unsigned)f2bf(a) | ((unsigned)f2bf(b) << 16); }
; __device__ __forceinline__ float bflo(unsigned w) { return __uint_as_float(w << 16); }
; __device__ __forceinline__ float bfhi(unsigned w) { return __uint_as_float(w & 0xffff0000u); }
; __device__ __forceinline__ float silu_f(float g) { return g / (1.f + __expf(-g)); }
; __device__ void gmlp_item(const Params& p, int layer, int b, int n, int g, char* smem) {
;     ...
; #pragma unroll
;     for (int i = 0; i < 8; ++i) {
;       int q = tid + 256 * i, t = q >> 4, c = (q & 15) * 8;
;       float4 m0 = *reinterpret_cast<const float4*>(Tf + t * 132 + c);
;       float4 m1 = *reinterpret_cast<const float4*>(Tf + t * 132 + c + 4);
;       float mm[8] = {m0.x, m0.y, m0.z, m0.w, m1.x, m1.y, m1.z, m1.w};
;       unsigned uw[4] = {uu[i].x, uu[i].y, uu[i].z, uu[i].w};
;       unsigned gw[4] = {gt[i].x, gt[i].y, gt[i].z, gt[i].w};
;       unsigned ow[4];
; #pragma unroll
;       for (int e = 0; e < 4; ++e) {
;         float y0 = bflo(uw[e]) * mm[2 * e] * silu_f(bflo(gw[e]));
;         float y1 = bfhi(uw[e]) * mm[2 * e + 1] * silu_f(bfhi(gw[e]));
;         ow[e] = pack2(y0, y1);
;       }
;       *reinterpret_cast<uint4*>(Y + (t0 + t) * YW + g * 128 + c) = make_uint4(ow[0], ow[1], ow[2], ow[3]);
	v_mov_b32_e32 v14, v8
	v_mov_b32_e32 v15, v10
	v_lshlrev_b32_e32 v63, 16, v3
	v_lshlrev_b32_e32 v62, 16, v2
	v_pk_mul_f32 v[14:15], v[14:15], v[62:63]
	v_rcp_f32_e32 v63, v65
	s_nop 0
	v_mul_f32_e32 v63, v13, v63
	v_mul_f32_e32 v10, 0xbfb8aa3b, v21
	v_exp_f32_e32 v61, v10
	v_rcp_f32_e32 v62, v64
	s_nop 0
	v_mul_f32_e32 v62, v17, v62
	v_mov_b32_e32 v10, v9
	v_and_b32_e32 v3, 0xffff0000, v3
	v_pk_add_f32 v[60:61], v[60:61], 1.0 op_sel_hi:[1,0]
	v_and_b32_e32 v2, 0xffff0000, v2
	v_pk_mul_f32 v[2:3], v[10:11], v[2:3]
	v_pk_mul_f32 v[14:15], v[62:63], v[14:15]
	v_rcp_f32_e32 v9, v61
	s_nop 0
	v_mul_f32_e32 v9, v21, v9
	v_rcp_f32_e32 v8, v60
	s_nop 0
	v_mul_f32_e32 v8, v25, v8
	v_pk_mul_f32 v[2:3], v[8:9], v[2:3]
	v_cvt_pk_bf16_f32 v3, 0, v3
	v_cvt_pk_bf16_f32 v8, 0, v15
	v_and_b32_e32 v3, 0xffff0000, v3
	v_or_b32_sdwa v3, v3, v8 dst_sel:DWORD dst_unused:UNUSED_PAD src0_sel:DWORD src1_sel:WORD_1
	v_cvt_pk_bf16_f32 v2, 0, v2
	v_cvt_pk_bf16_f32 v9, 0, v14
	v_and_b32_e32 v2, 0xffff0000, v2
	v_or_b32_sdwa v2, v2, v9 dst_sel:DWORD dst_unused:UNUSED_PAD src0_sel:DWORD src1_sel:WORD_1
	s_waitcnt vmcnt(0)
	v_lshlrev_b32_e32 v21, 16, v56
	v_mul_f32_e32 v8, 0xbfb8aa3b, v21
	v_and_b32_e32 v29, 0xffff0000, v56
	v_lshlrev_b32_e32 v17, 16, v57
	v_exp_f32_e32 v60, v8
	v_mul_f32_e32 v8, 0xbfb8aa3b, v29
	v_exp_f32_e32 v56, v8
	v_mul_f32_e32 v8, 0xbfb8aa3b, v17
	v_exp_f32_e32 v61, v8
	ds_read_b128 v[8:11], v12
	ds_read_b128 v[12:15], v12 offset:16
	v_and_b32_e32 v25, 0xffff0000, v57
	v_lshlrev_b32_e32 v63, 16, v5
	v_pk_add_f32 v[60:61], v[60:61], 1.0 op_sel_hi:[1,0]
	s_waitcnt lgkmcnt(1)
	v_mov_b32_e32 v64, v8
	v_mov_b32_e32 v65, v10
	v_lshlrev_b32_e32 v62, 16, v4
	v_and_b32_e32 v5, 0xffff0000, v5
	v_rcp_f32_e32 v61, v61
	s_nop 0
	v_mul_f32_e32 v61, v17, v61
	v_and_b32_e32 v4, 0xffff0000, v4
	v_mul_f32_e32 v10, 0xbfb8aa3b, v25
	v_exp_f32_e32 v57, v10
	v_rcp_f32_e32 v60, v60
	s_nop 0
	v_mul_f32_e32 v60, v21, v60
	v_mov_b32_e32 v10, v9
	v_pk_mul_f32 v[4:5], v[10:11], v[4:5]
	v_pk_add_f32 v[56:57], v[56:57], 1.0 op_sel_hi:[1,0]
	v_pk_mul_f32 v[62:63], v[64:65], v[62:63]
	v_pk_mul_f32 v[60:61], v[60:61], v[62:63]
	v_lshlrev_b32_e32 v63, 16, v7
	v_lshlrev_b32_e32 v62, 16, v6
	v_rcp_f32_e32 v9, v57
	s_nop 0
	v_mul_f32_e32 v9, v25, v9
	v_rcp_f32_e32 v8, v56
	s_nop 0
	v_mul_f32_e32 v8, v29, v8
	v_pk_mul_f32 v[4:5], v[8:9], v[4:5]
	v_cvt_pk_bf16_f32 v5, 0, v5
	v_cvt_pk_bf16_f32 v4, 0, v4
	v_cvt_pk_bf16_f32 v9, 0, v60
	v_cvt_pk_bf16_f32 v8, 0, v61
	v_and_b32_e32 v5, 0xffff0000, v5
	v_and_b32_e32 v4, 0xffff0000, v4
	v_lshlrev_b32_e32 v17, 16, v59
	v_lshlrev_b32_e32 v21, 16, v58
	v_or_b32_sdwa v5, v5, v8 dst_sel:DWORD dst_unused:UNUSED_PAD src0_sel:DWORD src1_sel:WORD_1
	v_or_b32_sdwa v4, v4, v9 dst_sel:DWORD dst_unused:UNUSED_PAD src0_sel:DWORD src1_sel:WORD_1
	v_mul_f32_e32 v8, 0xbfb8aa3b, v21
	v_mul_f32_e32 v9, 0xbfb8aa3b, v17
	v_exp_f32_e32 v8, v8
	v_exp_f32_e32 v9, v9
	v_and_b32_e32 v29, 0xffff0000, v58
	v_mul_f32_e32 v10, 0xbfb8aa3b, v29
	v_and_b32_e32 v25, 0xffff0000, v59
	v_exp_f32_e32 v60, v10
	v_pk_add_f32 v[64:65], v[8:9], 1.0 op_sel_hi:[1,0]
	global_load_dwordx4 v[8:11], v[18:19], off
	global_load_dwordx4 v[56:59], v[18:19], off offset:2048
	s_waitcnt lgkmcnt(0)
	v_mov_b32_e32 v18, v12
	v_mov_b32_e32 v19, v14
	v_pk_mul_f32 v[18:19], v[18:19], v[62:63]
	v_rcp_f32_e32 v63, v65
	s_nop 0
	v_mul_f32_e32 v63, v17, v63
	v_and_b32_e32 v7, 0xffff0000, v7
	v_mul_f32_e32 v14, 0xbfb8aa3b, v25
	v_exp_f32_e32 v61, v14
	v_rcp_f32_e32 v62, v64
	s_nop 0
	v_mul_f32_e32 v62, v21, v62
	v_mov_b32_e32 v14, v13
	v_and_b32_e32 v6, 0xffff0000, v6
	v_pk_add_f32 v[60:61], v[60:61], 1.0 op_sel_hi:[1,0]
	v_pk_mul_f32 v[6:7], v[14:15], v[6:7]
	v_pk_mul_f32 v[18:19], v[62:63], v[18:19]
	v_rcp_f32_e32 v13, v61
	s_nop 0
	v_mul_f32_e32 v13, v25, v13
	v_rcp_f32_e32 v12, v60
	s_nop 0
	v_mul_f32_e32 v12, v29, v12
	v_pk_mul_f32 v[6:7], v[12:13], v[6:7]
	v_cvt_pk_bf16_f32 v7, 0, v7
	v_cvt_pk_bf16_f32 v12, 0, v19
	v_and_b32_e32 v7, 0xffff0000, v7
	v_or_b32_sdwa v7, v7, v12 dst_sel:DWORD dst_unused:UNUSED_PAD src0_sel:DWORD src1_sel:WORD_1
	v_cvt_pk_bf16_f32 v6, 0, v6
	v_cvt_pk_bf16_f32 v13, 0, v18
	v_and_b32_e32 v6, 0xffff0000, v6
	v_or_b32_sdwa v6, v6, v13 dst_sel:DWORD dst_unused:UNUSED_PAD src0_sel:DWORD src1_sel:WORD_1
	s_waitcnt vmcnt(1)
	v_lshlrev_b32_e32 v63, 16, v9
	s_waitcnt vmcnt(0)
	v_lshlrev_b32_e32 v25, 16, v56
	v_mul_f32_e32 v12, 0xbfb8aa3b, v25
	v_and_b32_e32 v35, 0xffff0000, v56
	v_lshlrev_b32_e32 v21, 16, v57
	v_exp_f32_e32 v60, v12
	v_mul_f32_e32 v12, 0xbfb8aa3b, v35
	v_exp_f32_e32 v56, v12
	v_mul_f32_e32 v12, 0xbfb8aa3b, v21
	v_exp_f32_e32 v61, v12
	v_and_b32_e32 v29, 0xffff0000, v57
	ds_read_b128 v[12:15], v16
	ds_read_b128 v[16:19], v16 offset:16
	v_lshlrev_b32_e32 v62, 16, v8
	v_pk_add_f32 v[60:61], v[60:61], 1.0 op_sel_hi:[1,0]
	v_and_b32_e32 v9, 0xffff0000, v9
	s_waitcnt lgkmcnt(1)
	v_mov_b32_e32 v64, v12
	v_mov_b32_e32 v65, v14
	v_pk_mul_f32 v[62:63], v[64:65], v[62:63]
	v_rcp_f32_e32 v61, v61
	s_nop 0
	v_mul_f32_e32 v61, v21, v61
	v_and_b32_e32 v8, 0xffff0000, v8
	v_mul_f32_e32 v14, 0xbfb8aa3b, v29
	v_exp_f32_e32 v57, v14
	v_rcp_f32_e32 v60, v60
	s_nop 0
	v_mul_f32_e32 v60, v25, v60
	v_mov_b32_e32 v14, v13
	v_pk_mul_f32 v[8:9], v[14:15], v[8:9]
	v_pk_add_f32 v[56:57], v[56:57], 1.0 op_sel_hi:[1,0]
	v_pk_mul_f32 v[60:61], v[60:61], v[62:63]
	v_lshlrev_b32_e32 v63, 16, v11
	v_lshlrev_b32_e32 v62, 16, v10
	v_and_b32_e32 v11, 0xffff0000, v11
	v_rcp_f32_e32 v13, v57
	s_nop 0
	v_mul_f32_e32 v13, v29, v13
	v_rcp_f32_e32 v12, v56
	s_nop 0
	v_mul_f32_e32 v12, v35, v12
	v_pk_mul_f32 v[8:9], v[12:13], v[8:9]
	v_cvt_pk_bf16_f32 v9, 0, v9
	v_cvt_pk_bf16_f32 v8, 0, v8
	v_cvt_pk_bf16_f32 v13, 0, v60
	v_cvt_pk_bf16_f32 v12, 0, v61
	v_and_b32_e32 v9, 0xffff0000, v9
	v_and_b32_e32 v8, 0xffff0000, v8
	v_lshlrev_b32_e32 v21, 16, v59
	v_lshlrev_b32_e32 v25, 16, v58
	v_or_b32_sdwa v9, v9, v12 dst_sel:DWORD dst_unused:UNUSED_PAD src0_sel:DWORD src1_sel:WORD_1
	v_or_b32_sdwa v8, v8, v13 dst_sel:DWORD dst_unused:UNUSED_PAD src0_sel:DWORD src1_sel:WORD_1
	v_mul_f32_e32 v12, 0xbfb8aa3b, v25
	v_mul_f32_e32 v13, 0xbfb8aa3b, v21
	v_exp_f32_e32 v12, v12
	v_exp_f32_e32 v13, v13
	v_and_b32_e32 v35, 0xffff0000, v58
	v_mul_f32_e32 v14, 0xbfb8aa3b, v35
	v_and_b32_e32 v29, 0xffff0000, v59
	v_exp_f32_e32 v60, v14
	v_pk_add_f32 v[64:65], v[12:13], 1.0 op_sel_hi:[1,0]
	global_load_dwordx4 v[12:15], v[22:23], off
	global_load_dwordx4 v[56:59], v[22:23], off offset:2048
	s_waitcnt lgkmcnt(0)
; __device__ __forceinline__ unsigned pack2(float a, float b) { return (unsigned)f2bf(a) | ((unsigned)f2bf(b) << 16); }
; __device__ __forceinline__ float bflo(unsigned w) { return __uint_as_float(w << 16); }
; __device__ __forceinline__ float bfhi(unsigned w) { return __uint_as_float(w & 0xffff0000u); }
; __device__ __forceinline__ float silu_f(float g) { return g / (1.f + __expf(-g)); }
; __device__ void gmlp_item(const Params& p, int layer, int b, int n, int g, char* smem) {
;     ...
; #pragma unroll
;     for (int i = 0; i < 8; ++i) {
;       int q = tid + 256 * i, t = q >> 4, c = (q & 15) * 8;
;       float4 m0 = *reinterpret_cast<const float4*>(Tf + t * 132 + c);
;       float4 m1 = *reinterpret_cast<const float4*>(Tf + t * 132 + c + 4);
;       float mm[8] = {m0.x, m0.y, m0.z, m0.w, m1.x, m1.y, m1.z, m1.w};
;       unsigned uw[4] = {uu[i].x, uu[i].y, uu[i].z, uu[i].w};
;       unsigned gw[4] = {gt[i].x, gt[i].y, gt[i].z, gt[i].w};
;       unsigned ow[4];
; #pragma unroll
;       for (int e = 0; e < 4; ++e) {
;         float y0 = bflo(uw[e]) * mm[2 * e] * silu_f(bflo(gw[e]));
;         float y1 = bfhi(uw[e]) * mm[2 * e + 1] * silu_f(bfhi(gw[e]));
;         ow[e] = pack2(y0, y1);
;       }
;       *reinterpret_cast<uint4*>(Y + (t0 + t) * YW + g * 128 + c) = make_uint4(ow[0], ow[1], ow[2], ow[3]);
	v_mov_b32_e32 v22, v16
	v_mov_b32_e32 v23, v18
	v_pk_mul_f32 v[22:23], v[22:23], v[62:63]
	v_rcp_f32_e32 v63, v65
	s_nop 0
	v_mul_f32_e32 v63, v21, v63
	v_and_b32_e32 v10, 0xffff0000, v10
	v_mul_f32_e32 v18, 0xbfb8aa3b, v29
	v_exp_f32_e32 v61, v18
	v_rcp_f32_e32 v62, v64
	s_nop 0
	v_mul_f32_e32 v62, v25, v62
	v_mov_b32_e32 v18, v17
	v_pk_mul_f32 v[10:11], v[18:19], v[10:11]
	v_pk_add_f32 v[60:61], v[60:61], 1.0 op_sel_hi:[1,0]
	v_pk_mul_f32 v[22:23], v[62:63], v[22:23]
	s_waitcnt vmcnt(1)
	v_lshlrev_b32_e32 v63, 16, v13
	v_rcp_f32_e32 v17, v61
	s_nop 0
	v_mul_f32_e32 v17, v29, v17
	v_rcp_f32_e32 v16, v60
	s_nop 0
	v_mul_f32_e32 v16, v35, v16
	v_pk_mul_f32 v[10:11], v[16:17], v[10:11]
	v_cvt_pk_bf16_f32 v11, 0, v11
	v_cvt_pk_bf16_f32 v16, 0, v23
	v_and_b32_e32 v11, 0xffff0000, v11
	s_waitcnt vmcnt(0)
	v_lshlrev_b32_e32 v29, 16, v56
	v_or_b32_sdwa v11, v11, v16 dst_sel:DWORD dst_unused:UNUSED_PAD src0_sel:DWORD src1_sel:WORD_1
	v_mul_f32_e32 v16, 0xbfb8aa3b, v29
	v_and_b32_e32 v55, 0xffff0000, v56
	v_lshlrev_b32_e32 v25, 16, v57
	v_exp_f32_e32 v60, v16
	v_mul_f32_e32 v16, 0xbfb8aa3b, v55
	v_exp_f32_e32 v56, v16
	v_mul_f32_e32 v16, 0xbfb8aa3b, v25
	v_exp_f32_e32 v61, v16
	v_cvt_pk_bf16_f32 v10, 0, v10
	v_pk_add_f32 v[60:61], v[60:61], 1.0 op_sel_hi:[1,0]
	v_cvt_pk_bf16_f32 v17, 0, v22
	v_and_b32_e32 v10, 0xffff0000, v10
	v_and_b32_e32 v35, 0xffff0000, v57
	v_or_b32_sdwa v10, v10, v17 dst_sel:DWORD dst_unused:UNUSED_PAD src0_sel:DWORD src1_sel:WORD_1
	ds_read_b128 v[16:19], v20
	ds_read_b128 v[20:23], v20 offset:16
	v_lshlrev_b32_e32 v62, 16, v12
	v_and_b32_e32 v13, 0xffff0000, v13
	s_waitcnt lgkmcnt(1)
	v_mov_b32_e32 v64, v16
	v_mov_b32_e32 v65, v18
	v_pk_mul_f32 v[62:63], v[64:65], v[62:63]
	v_rcp_f32_e32 v61, v61
	s_nop 0
	v_mul_f32_e32 v61, v25, v61
	v_and_b32_e32 v12, 0xffff0000, v12
	v_mul_f32_e32 v18, 0xbfb8aa3b, v35
	v_exp_f32_e32 v57, v18
	v_rcp_f32_e32 v60, v60
	s_nop 0
	v_mul_f32_e32 v60, v29, v60
	v_mov_b32_e32 v18, v17
	v_pk_mul_f32 v[12:13], v[18:19], v[12:13]
	v_pk_add_f32 v[56:57], v[56:57], 1.0 op_sel_hi:[1,0]
	v_pk_mul_f32 v[60:61], v[60:61], v[62:63]
	v_lshlrev_b32_e32 v63, 16, v15
	v_lshlrev_b32_e32 v62, 16, v14
	v_and_b32_e32 v15, 0xffff0000, v15
	v_rcp_f32_e32 v17, v57
	s_nop 0
	v_mul_f32_e32 v17, v35, v17
	v_rcp_f32_e32 v16, v56
	s_nop 0
	v_mul_f32_e32 v16, v55, v16
	v_pk_mul_f32 v[12:13], v[16:17], v[12:13]
	v_cvt_pk_bf16_f32 v13, 0, v13
	v_cvt_pk_bf16_f32 v12, 0, v12
	v_cvt_pk_bf16_f32 v17, 0, v60
	v_cvt_pk_bf16_f32 v16, 0, v61
	v_and_b32_e32 v13, 0xffff0000, v13
	v_and_b32_e32 v12, 0xffff0000, v12
	v_lshlrev_b32_e32 v25, 16, v59
	v_lshlrev_b32_e32 v29, 16, v58
	v_or_b32_sdwa v13, v13, v16 dst_sel:DWORD dst_unused:UNUSED_PAD src0_sel:DWORD src1_sel:WORD_1
	v_or_b32_sdwa v12, v12, v17 dst_sel:DWORD dst_unused:UNUSED_PAD src0_sel:DWORD src1_sel:WORD_1
	v_mul_f32_e32 v16, 0xbfb8aa3b, v29
	v_mul_f32_e32 v17, 0xbfb8aa3b, v25
	v_exp_f32_e32 v16, v16
	v_exp_f32_e32 v17, v17
	v_and_b32_e32 v55, 0xffff0000, v58
	v_mul_f32_e32 v18, 0xbfb8aa3b, v55
	v_and_b32_e32 v35, 0xffff0000, v59
	v_exp_f32_e32 v60, v18
	v_pk_add_f32 v[64:65], v[16:17], 1.0 op_sel_hi:[1,0]
	global_load_dwordx4 v[16:19], v[26:27], off
	global_load_dwordx4 v[56:59], v[26:27], off offset:2048
	s_waitcnt lgkmcnt(0)
	v_mov_b32_e32 v26, v20
	v_mov_b32_e32 v27, v22
	v_pk_mul_f32 v[26:27], v[26:27], v[62:63]
	v_rcp_f32_e32 v63, v65
	s_nop 0
	v_mul_f32_e32 v63, v25, v63
	v_and_b32_e32 v14, 0xffff0000, v14
	v_mul_f32_e32 v22, 0xbfb8aa3b, v35
	v_exp_f32_e32 v61, v22
	v_rcp_f32_e32 v62, v64
	s_nop 0
	v_mul_f32_e32 v62, v29, v62
	v_mov_b32_e32 v22, v21
	v_pk_mul_f32 v[14:15], v[22:23], v[14:15]
	v_pk_add_f32 v[60:61], v[60:61], 1.0 op_sel_hi:[1,0]
	v_pk_mul_f32 v[26:27], v[62:63], v[26:27]
	s_waitcnt vmcnt(1)
	v_lshlrev_b32_e32 v63, 16, v17
	v_rcp_f32_e32 v21, v61
	s_nop 0
	v_mul_f32_e32 v21, v35, v21
	v_rcp_f32_e32 v20, v60
	s_nop 0
	v_mul_f32_e32 v20, v55, v20
	v_pk_mul_f32 v[14:15], v[20:21], v[14:15]
	v_cvt_pk_bf16_f32 v15, 0, v15
	v_cvt_pk_bf16_f32 v20, 0, v27
	v_and_b32_e32 v15, 0xffff0000, v15
	s_waitcnt vmcnt(0)
	v_lshlrev_b32_e32 v35, 16, v56
	v_or_b32_sdwa v15, v15, v20 dst_sel:DWORD dst_unused:UNUSED_PAD src0_sel:DWORD src1_sel:WORD_1
	v_mul_f32_e32 v20, 0xbfb8aa3b, v35
	v_and_b32_e32 v66, 0xffff0000, v56
	v_lshlrev_b32_e32 v29, 16, v57
	v_exp_f32_e32 v60, v20
	v_mul_f32_e32 v20, 0xbfb8aa3b, v66
	v_exp_f32_e32 v56, v20
	v_mul_f32_e32 v20, 0xbfb8aa3b, v29
	v_exp_f32_e32 v61, v20
	v_cvt_pk_bf16_f32 v14, 0, v14
	v_pk_add_f32 v[60:61], v[60:61], 1.0 op_sel_hi:[1,0]
	v_cvt_pk_bf16_f32 v21, 0, v26
	v_and_b32_e32 v14, 0xffff0000, v14
	v_and_b32_e32 v55, 0xffff0000, v57
	v_or_b32_sdwa v14, v14, v21 dst_sel:DWORD dst_unused:UNUSED_PAD src0_sel:DWORD src1_sel:WORD_1
	ds_read_b128 v[20:23], v24
	ds_read_b128 v[24:27], v24 offset:16
	v_lshlrev_b32_e32 v62, 16, v16
	v_and_b32_e32 v17, 0xffff0000, v17
	s_waitcnt lgkmcnt(1)
; __device__ __forceinline__ unsigned pack2(float a, float b) { return (unsigned)f2bf(a) | ((unsigned)f2bf(b) << 16); }
; __device__ __forceinline__ float bflo(unsigned w) { return __uint_as_float(w << 16); }
; __device__ __forceinline__ float bfhi(unsigned w) { return __uint_as_float(w & 0xffff0000u); }
; __device__ __forceinline__ float silu_f(float g) { return g / (1.f + __expf(-g)); }
; __device__ void gmlp_item(const Params& p, int layer, int b, int n, int g, char* smem) {
;     ...
; #pragma unroll
;     for (int i = 0; i < 8; ++i) {
;       int q = tid + 256 * i, t = q >> 4, c = (q & 15) * 8;
;       float4 m0 = *reinterpret_cast<const float4*>(Tf + t * 132 + c);
;       float4 m1 = *reinterpret_cast<const float4*>(Tf + t * 132 + c + 4);
;       float mm[8] = {m0.x, m0.y, m0.z, m0.w, m1.x, m1.y, m1.z, m1.w};
;       unsigned uw[4] = {uu[i].x, uu[i].y, uu[i].z, uu[i].w};
;       unsigned gw[4] = {gt[i].x, gt[i].y, gt[i].z, gt[i].w};
;       unsigned ow[4];
; #pragma unroll
;       for (int e = 0; e < 4; ++e) {
;         float y0 = bflo(uw[e]) * mm[2 * e] * silu_f(bflo(gw[e]));
;         float y1 = bfhi(uw[e]) * mm[2 * e + 1] * silu_f(bfhi(gw[e]));
;         ow[e] = pack2(y0, y1);
;       }
;       *reinterpret_cast<uint4*>(Y + (t0 + t) * YW + g * 128 + c) = make_uint4(ow[0], ow[1], ow[2], ow[3]);
	v_mov_b32_e32 v64, v20
	v_mov_b32_e32 v65, v22
	v_pk_mul_f32 v[62:63], v[64:65], v[62:63]
	v_rcp_f32_e32 v61, v61
	s_nop 0
	v_mul_f32_e32 v61, v29, v61
	v_and_b32_e32 v16, 0xffff0000, v16
	v_mul_f32_e32 v22, 0xbfb8aa3b, v55
	v_exp_f32_e32 v57, v22
	v_rcp_f32_e32 v60, v60
	s_nop 0
	v_mul_f32_e32 v60, v35, v60
	v_mov_b32_e32 v22, v21
	v_pk_mul_f32 v[16:17], v[22:23], v[16:17]
	v_pk_add_f32 v[56:57], v[56:57], 1.0 op_sel_hi:[1,0]
	v_pk_mul_f32 v[60:61], v[60:61], v[62:63]
	v_lshlrev_b32_e32 v63, 16, v19
	v_lshlrev_b32_e32 v62, 16, v18
	v_and_b32_e32 v19, 0xffff0000, v19
	v_rcp_f32_e32 v21, v57
	s_nop 0
	v_mul_f32_e32 v21, v55, v21
	v_rcp_f32_e32 v20, v56
	s_nop 0
	v_mul_f32_e32 v20, v66, v20
	v_pk_mul_f32 v[16:17], v[20:21], v[16:17]
	v_cvt_pk_bf16_f32 v17, 0, v17
	v_cvt_pk_bf16_f32 v16, 0, v16
	v_cvt_pk_bf16_f32 v21, 0, v60
	v_cvt_pk_bf16_f32 v20, 0, v61
	v_and_b32_e32 v17, 0xffff0000, v17
	v_and_b32_e32 v16, 0xffff0000, v16
	v_lshlrev_b32_e32 v29, 16, v59
	v_lshlrev_b32_e32 v35, 16, v58
	v_or_b32_sdwa v17, v17, v20 dst_sel:DWORD dst_unused:UNUSED_PAD src0_sel:DWORD src1_sel:WORD_1
	v_or_b32_sdwa v16, v16, v21 dst_sel:DWORD dst_unused:UNUSED_PAD src0_sel:DWORD src1_sel:WORD_1
	v_mul_f32_e32 v20, 0xbfb8aa3b, v35
	v_mul_f32_e32 v21, 0xbfb8aa3b, v29
	v_exp_f32_e32 v20, v20
	v_exp_f32_e32 v21, v21
	v_and_b32_e32 v66, 0xffff0000, v58
	v_mul_f32_e32 v22, 0xbfb8aa3b, v66
	v_and_b32_e32 v55, 0xffff0000, v59
	v_exp_f32_e32 v60, v22
	v_pk_add_f32 v[64:65], v[20:21], 1.0 op_sel_hi:[1,0]
	global_load_dwordx4 v[20:23], v[30:31], off
	global_load_dwordx4 v[56:59], v[30:31], off offset:2048
	s_waitcnt lgkmcnt(0)
	v_mov_b32_e32 v30, v24
	v_mov_b32_e32 v31, v26
	v_pk_mul_f32 v[30:31], v[30:31], v[62:63]
	v_rcp_f32_e32 v63, v65
	s_nop 0
	v_mul_f32_e32 v63, v29, v63
	v_and_b32_e32 v18, 0xffff0000, v18
	v_mul_f32_e32 v26, 0xbfb8aa3b, v55
	v_exp_f32_e32 v61, v26
	v_rcp_f32_e32 v62, v64
	s_nop 0
	v_mul_f32_e32 v62, v35, v62
	v_mov_b32_e32 v26, v25
	v_pk_mul_f32 v[18:19], v[26:27], v[18:19]
	v_pk_add_f32 v[60:61], v[60:61], 1.0 op_sel_hi:[1,0]
	v_pk_mul_f32 v[30:31], v[62:63], v[30:31]
	s_waitcnt vmcnt(1)
	v_lshlrev_b32_e32 v63, 16, v21
	v_rcp_f32_e32 v25, v61
	s_nop 0
	v_mul_f32_e32 v25, v55, v25
	v_rcp_f32_e32 v24, v60
	s_nop 0
	v_mul_f32_e32 v24, v66, v24
	v_pk_mul_f32 v[18:19], v[24:25], v[18:19]
	v_cvt_pk_bf16_f32 v19, 0, v19
	v_cvt_pk_bf16_f32 v24, 0, v31
	v_and_b32_e32 v19, 0xffff0000, v19
	s_waitcnt vmcnt(0)
	v_lshlrev_b32_e32 v55, 16, v56
	v_or_b32_sdwa v19, v19, v24 dst_sel:DWORD dst_unused:UNUSED_PAD src0_sel:DWORD src1_sel:WORD_1
	v_mul_f32_e32 v24, 0xbfb8aa3b, v55
	v_and_b32_e32 v67, 0xffff0000, v56
	v_lshlrev_b32_e32 v35, 16, v57
	v_exp_f32_e32 v60, v24
	v_mul_f32_e32 v24, 0xbfb8aa3b, v67
	v_exp_f32_e32 v56, v24
	v_mul_f32_e32 v24, 0xbfb8aa3b, v35
	v_exp_f32_e32 v61, v24
	v_cvt_pk_bf16_f32 v18, 0, v18
	v_pk_add_f32 v[60:61], v[60:61], 1.0 op_sel_hi:[1,0]
	v_cvt_pk_bf16_f32 v25, 0, v30
	v_and_b32_e32 v18, 0xffff0000, v18
	v_and_b32_e32 v66, 0xffff0000, v57
	v_or_b32_sdwa v18, v18, v25 dst_sel:DWORD dst_unused:UNUSED_PAD src0_sel:DWORD src1_sel:WORD_1
	ds_read_b128 v[24:27], v28
	ds_read_b128 v[28:31], v28 offset:16
	v_lshlrev_b32_e32 v62, 16, v20
	v_and_b32_e32 v21, 0xffff0000, v21
	s_waitcnt lgkmcnt(1)
	v_mov_b32_e32 v64, v24
	v_mov_b32_e32 v65, v26
	v_pk_mul_f32 v[62:63], v[64:65], v[62:63]
	v_rcp_f32_e32 v61, v61
	s_nop 0
	v_mul_f32_e32 v61, v35, v61
	v_and_b32_e32 v20, 0xffff0000, v20
	v_mul_f32_e32 v26, 0xbfb8aa3b, v66
	v_exp_f32_e32 v57, v26
	v_rcp_f32_e32 v60, v60
	s_nop 0
	v_mul_f32_e32 v60, v55, v60
	v_mov_b32_e32 v26, v25
	v_pk_mul_f32 v[20:21], v[26:27], v[20:21]
	v_pk_add_f32 v[56:57], v[56:57], 1.0 op_sel_hi:[1,0]
	v_pk_mul_f32 v[60:61], v[60:61], v[62:63]
	v_lshlrev_b32_e32 v63, 16, v23
	v_lshlrev_b32_e32 v62, 16, v22
	v_and_b32_e32 v23, 0xffff0000, v23
	v_rcp_f32_e32 v25, v57
	s_nop 0
	v_mul_f32_e32 v25, v66, v25
	v_rcp_f32_e32 v24, v56
	s_nop 0
	v_mul_f32_e32 v24, v67, v24
	v_pk_mul_f32 v[20:21], v[24:25], v[20:21]
	v_cvt_pk_bf16_f32 v21, 0, v21
	v_cvt_pk_bf16_f32 v20, 0, v20
	v_cvt_pk_bf16_f32 v25, 0, v60
	v_cvt_pk_bf16_f32 v24, 0, v61
	v_and_b32_e32 v21, 0xffff0000, v21
	v_and_b32_e32 v20, 0xffff0000, v20
	v_lshlrev_b32_e32 v35, 16, v59
	v_lshlrev_b32_e32 v55, 16, v58
	v_or_b32_sdwa v21, v21, v24 dst_sel:DWORD dst_unused:UNUSED_PAD src0_sel:DWORD src1_sel:WORD_1
	v_or_b32_sdwa v20, v20, v25 dst_sel:DWORD dst_unused:UNUSED_PAD src0_sel:DWORD src1_sel:WORD_1
	v_mul_f32_e32 v24, 0xbfb8aa3b, v55
	v_mul_f32_e32 v25, 0xbfb8aa3b, v35
	v_exp_f32_e32 v24, v24
	v_exp_f32_e32 v25, v25
	v_and_b32_e32 v67, 0xffff0000, v58
	v_mul_f32_e32 v26, 0xbfb8aa3b, v67
	v_and_b32_e32 v66, 0xffff0000, v59
	v_exp_f32_e32 v60, v26
	v_pk_add_f32 v[64:65], v[24:25], 1.0 op_sel_hi:[1,0]
	global_load_dwordx4 v[24:27], v[32:33], off
	global_load_dwordx4 v[56:59], v[32:33], off offset:2048
	s_waitcnt lgkmcnt(0)
	v_mov_b32_e32 v32, v28
	v_mov_b32_e32 v33, v30
	v_pk_mul_f32 v[32:33], v[32:33], v[62:63]
	v_rcp_f32_e32 v63, v65
	s_nop 0
	v_mul_f32_e32 v63, v35, v63
	v_and_b32_e32 v22, 0xffff0000, v22
	v_mul_f32_e32 v30, 0xbfb8aa3b, v66
	v_exp_f32_e32 v61, v30
	v_rcp_f32_e32 v62, v64
	s_nop 0
	v_mul_f32_e32 v62, v55, v62
	v_mov_b32_e32 v30, v29
	v_pk_mul_f32 v[22:23], v[30:31], v[22:23]
	v_pk_add_f32 v[60:61], v[60:61], 1.0 op_sel_hi:[1,0]
	v_pk_mul_f32 v[32:33], v[62:63], v[32:33]
	s_waitcnt vmcnt(1)
	v_lshlrev_b32_e32 v63, 16, v25
	v_rcp_f32_e32 v29, v61
	s_nop 0
	v_mul_f32_e32 v29, v66, v29
	v_rcp_f32_e32 v28, v60
	s_nop 0
	v_mul_f32_e32 v28, v67, v28
	v_pk_mul_f32 v[22:23], v[28:29], v[22:23]
	v_cvt_pk_bf16_f32 v23, 0, v23
	v_cvt_pk_bf16_f32 v28, 0, v33
	v_and_b32_e32 v23, 0xffff0000, v23
	s_waitcnt vmcnt(0)
; __device__ __forceinline__ unsigned pack2(float a, float b) { return (unsigned)f2bf(a) | ((unsigned)f2bf(b) << 16); }
; __device__ __forceinline__ float bflo(unsigned w) { return __uint_as_float(w << 16); }
; __device__ __forceinline__ float bfhi(unsigned w) { return __uint_as_float(w & 0xffff0000u); }
; __device__ __forceinline__ float silu_f(float g) { return g / (1.f + __expf(-g)); }
; __device__ void gmlp_item(const Params& p, int layer, int b, int n, int g, char* smem) {
;     ...
; #pragma unroll
;     for (int i = 0; i < 8; ++i) {
;       int q = tid + 256 * i, t = q >> 4, c = (q & 15) * 8;
;       float4 m0 = *reinterpret_cast<const float4*>(Tf + t * 132 + c);
;       float4 m1 = *reinterpret_cast<const float4*>(Tf + t * 132 + c + 4);
;       float mm[8] = {m0.x, m0.y, m0.z, m0.w, m1.x, m1.y, m1.z, m1.w};
;       unsigned uw[4] = {uu[i].x, uu[i].y, uu[i].z, uu[i].w};
;       unsigned gw[4] = {gt[i].x, gt[i].y, gt[i].z, gt[i].w};
;       unsigned ow[4];
; #pragma unroll
;       for (int e = 0; e < 4; ++e) {
;         float y0 = bflo(uw[e]) * mm[2 * e] * silu_f(bflo(gw[e]));
;         float y1 = bfhi(uw[e]) * mm[2 * e + 1] * silu_f(bfhi(gw[e]));
;         ow[e] = pack2(y0, y1);
;       }
;       *reinterpret_cast<uint4*>(Y + (t0 + t) * YW + g * 128 + c) = make_uint4(ow[0], ow[1], ow[2], ow[3]);
;     }
;   }
;   __syncthreads();
	v_lshlrev_b32_e32 v66, 16, v56
	v_or_b32_sdwa v23, v23, v28 dst_sel:DWORD dst_unused:UNUSED_PAD src0_sel:DWORD src1_sel:WORD_1
	v_mul_f32_e32 v28, 0xbfb8aa3b, v66
	v_and_b32_e32 v68, 0xffff0000, v56
	v_lshlrev_b32_e32 v55, 16, v57
	v_exp_f32_e32 v60, v28
	v_mul_f32_e32 v28, 0xbfb8aa3b, v68
	v_exp_f32_e32 v56, v28
	v_mul_f32_e32 v28, 0xbfb8aa3b, v55
	v_exp_f32_e32 v61, v28
	v_cvt_pk_bf16_f32 v22, 0, v22
	v_pk_add_f32 v[60:61], v[60:61], 1.0 op_sel_hi:[1,0]
	v_cvt_pk_bf16_f32 v29, 0, v32
	v_and_b32_e32 v22, 0xffff0000, v22
	v_and_b32_e32 v67, 0xffff0000, v57
	v_or_b32_sdwa v22, v22, v29 dst_sel:DWORD dst_unused:UNUSED_PAD src0_sel:DWORD src1_sel:WORD_1
	ds_read_b128 v[28:31], v34
	ds_read_b128 v[32:35], v34 offset:16
	v_lshlrev_b32_e32 v62, 16, v24
	v_and_b32_e32 v25, 0xffff0000, v25
	s_waitcnt lgkmcnt(1)
	v_mov_b32_e32 v64, v28
	v_mov_b32_e32 v65, v30
	v_pk_mul_f32 v[62:63], v[64:65], v[62:63]
	v_rcp_f32_e32 v61, v61
	s_nop 0
	v_mul_f32_e32 v61, v55, v61
	v_and_b32_e32 v24, 0xffff0000, v24
	v_mul_f32_e32 v30, 0xbfb8aa3b, v67
	v_exp_f32_e32 v57, v30
	v_rcp_f32_e32 v60, v60
	s_nop 0
	v_mul_f32_e32 v60, v66, v60
	v_mov_b32_e32 v30, v29
	v_pk_mul_f32 v[24:25], v[30:31], v[24:25]
	v_pk_add_f32 v[56:57], v[56:57], 1.0 op_sel_hi:[1,0]
	v_pk_mul_f32 v[60:61], v[60:61], v[62:63]
	v_lshlrev_b32_e32 v66, 16, v58
	v_lshlrev_b32_e32 v63, 16, v27
	v_and_b32_e32 v27, 0xffff0000, v27
	v_rcp_f32_e32 v29, v57
	s_nop 0
	v_mul_f32_e32 v29, v67, v29
	v_rcp_f32_e32 v28, v56
	s_nop 0
	v_mul_f32_e32 v28, v68, v28
	v_pk_mul_f32 v[24:25], v[28:29], v[24:25]
	v_cvt_pk_bf16_f32 v25, 0, v25
	v_cvt_pk_bf16_f32 v24, 0, v24
	v_cvt_pk_bf16_f32 v29, 0, v60
	v_cvt_pk_bf16_f32 v28, 0, v61
	v_and_b32_e32 v25, 0xffff0000, v25
	v_and_b32_e32 v24, 0xffff0000, v24
	v_lshlrev_b32_e32 v55, 16, v59
	v_or_b32_sdwa v25, v25, v28 dst_sel:DWORD dst_unused:UNUSED_PAD src0_sel:DWORD src1_sel:WORD_1
	v_or_b32_sdwa v24, v24, v29 dst_sel:DWORD dst_unused:UNUSED_PAD src0_sel:DWORD src1_sel:WORD_1
	v_mul_f32_e32 v28, 0xbfb8aa3b, v66
	v_mul_f32_e32 v29, 0xbfb8aa3b, v55
	v_exp_f32_e32 v28, v28
	v_exp_f32_e32 v29, v29
	v_and_b32_e32 v68, 0xffff0000, v58
	v_mul_f32_e32 v30, 0xbfb8aa3b, v68
	v_and_b32_e32 v67, 0xffff0000, v59
	v_exp_f32_e32 v60, v30
	v_pk_add_f32 v[64:65], v[28:29], 1.0 op_sel_hi:[1,0]
	global_load_dwordx4 v[28:31], v[52:53], off
	global_load_dwordx4 v[56:59], v[52:53], off offset:2048
	s_waitcnt lgkmcnt(0)
	v_mov_b32_e32 v52, v32
	v_lshlrev_b32_e32 v62, 16, v26
	v_mov_b32_e32 v53, v34
	v_pk_mul_f32 v[52:53], v[52:53], v[62:63]
	v_rcp_f32_e32 v63, v65
	s_nop 0
	v_mul_f32_e32 v63, v55, v63
	v_and_b32_e32 v26, 0xffff0000, v26
	v_mul_f32_e32 v34, 0xbfb8aa3b, v67
	v_exp_f32_e32 v61, v34
	v_rcp_f32_e32 v62, v64
	s_nop 0
	v_mul_f32_e32 v62, v66, v62
	v_mov_b32_e32 v34, v33
	v_pk_mul_f32 v[26:27], v[34:35], v[26:27]
	v_pk_add_f32 v[60:61], v[60:61], 1.0 op_sel_hi:[1,0]
	v_pk_mul_f32 v[52:53], v[62:63], v[52:53]
	s_waitcnt vmcnt(1)
	v_lshlrev_b32_e32 v63, 16, v29
	v_rcp_f32_e32 v33, v61
	s_nop 0
	v_mul_f32_e32 v33, v67, v33
	v_rcp_f32_e32 v32, v60
	s_nop 0
	v_mul_f32_e32 v32, v68, v32
	v_pk_mul_f32 v[26:27], v[32:33], v[26:27]
	v_cvt_pk_bf16_f32 v27, 0, v27
	v_cvt_pk_bf16_f32 v32, 0, v53
	v_and_b32_e32 v27, 0xffff0000, v27
	s_waitcnt vmcnt(0)
	v_lshlrev_b32_e32 v67, 16, v56
	v_or_b32_sdwa v27, v27, v32 dst_sel:DWORD dst_unused:UNUSED_PAD src0_sel:DWORD src1_sel:WORD_1
	v_mul_f32_e32 v32, 0xbfb8aa3b, v67
	v_and_b32_e32 v69, 0xffff0000, v56
	v_lshlrev_b32_e32 v66, 16, v57
	v_exp_f32_e32 v60, v32
	v_mul_f32_e32 v32, 0xbfb8aa3b, v69
	v_exp_f32_e32 v56, v32
	v_mul_f32_e32 v32, 0xbfb8aa3b, v66
	v_exp_f32_e32 v61, v32
	v_cvt_pk_bf16_f32 v26, 0, v26
	v_pk_add_f32 v[60:61], v[60:61], 1.0 op_sel_hi:[1,0]
	v_cvt_pk_bf16_f32 v33, 0, v52
	v_and_b32_e32 v26, 0xffff0000, v26
	v_and_b32_e32 v68, 0xffff0000, v57
	v_or_b32_sdwa v26, v26, v33 dst_sel:DWORD dst_unused:UNUSED_PAD src0_sel:DWORD src1_sel:WORD_1
	ds_read_b128 v[32:35], v54
	ds_read_b128 v[52:55], v54 offset:16
	v_lshlrev_b32_e32 v62, 16, v28
	v_and_b32_e32 v29, 0xffff0000, v29
	s_waitcnt lgkmcnt(1)
	v_mov_b32_e32 v64, v32
	v_mov_b32_e32 v65, v34
	v_pk_mul_f32 v[62:63], v[64:65], v[62:63]
	v_rcp_f32_e32 v61, v61
	s_nop 0
	v_mul_f32_e32 v61, v66, v61
	v_and_b32_e32 v28, 0xffff0000, v28
	v_mul_f32_e32 v34, 0xbfb8aa3b, v68
	v_exp_f32_e32 v57, v34
	v_rcp_f32_e32 v60, v60
	s_nop 0
	v_mul_f32_e32 v60, v67, v60
	v_pk_mul_f32 v[60:61], v[60:61], v[62:63]
	v_mov_b32_e32 v34, v33
	v_pk_add_f32 v[56:57], v[56:57], 1.0 op_sel_hi:[1,0]
	v_pk_mul_f32 v[28:29], v[34:35], v[28:29]
	s_nop 0
	v_rcp_f32_e32 v33, v57
	s_nop 0
	v_mul_f32_e32 v33, v68, v33
	v_rcp_f32_e32 v32, v56
	s_nop 0
	v_mul_f32_e32 v32, v69, v32
	v_pk_mul_f32 v[28:29], v[32:33], v[28:29]
	v_cvt_pk_bf16_f32 v29, 0, v29
	v_cvt_pk_bf16_f32 v28, 0, v28
	v_cvt_pk_bf16_f32 v33, 0, v60
	v_cvt_pk_bf16_f32 v32, 0, v61
	v_and_b32_e32 v29, 0xffff0000, v29
	v_and_b32_e32 v28, 0xffff0000, v28
	v_lshlrev_b32_e32 v35, 16, v59
	v_lshlrev_b32_e32 v60, 16, v58
	v_or_b32_sdwa v29, v29, v32 dst_sel:DWORD dst_unused:UNUSED_PAD src0_sel:DWORD src1_sel:WORD_1
	v_or_b32_sdwa v28, v28, v33 dst_sel:DWORD dst_unused:UNUSED_PAD src0_sel:DWORD src1_sel:WORD_1
	v_mul_f32_e32 v32, 0xbfb8aa3b, v60
	v_mul_f32_e32 v33, 0xbfb8aa3b, v35
	v_exp_f32_e32 v32, v32
	v_exp_f32_e32 v33, v33
	v_and_b32_e32 v62, 0xffff0000, v58
	s_waitcnt lgkmcnt(0)
	v_mov_b32_e32 v58, v52
	v_and_b32_e32 v61, 0xffff0000, v59
	v_pk_add_f32 v[32:33], v[32:33], 1.0 op_sel_hi:[1,0]
	v_lshlrev_b32_e32 v57, 16, v31
	v_lshlrev_b32_e32 v56, 16, v30
	v_mov_b32_e32 v59, v54
	v_pk_mul_f32 v[56:57], v[58:59], v[56:57]
	v_rcp_f32_e32 v33, v33
	s_nop 0
	v_mul_f32_e32 v33, v35, v33
	v_mul_f32_e32 v34, 0xbfb8aa3b, v62
	v_mul_f32_e32 v35, 0xbfb8aa3b, v61
	v_exp_f32_e32 v34, v34
	v_exp_f32_e32 v35, v35
	v_rcp_f32_e32 v32, v32
	s_nop 0
	v_mul_f32_e32 v32, v60, v32
	v_pk_mul_f32 v[32:33], v[32:33], v[56:57]
	v_mov_b32_e32 v54, v53
	v_pk_add_f32 v[34:35], v[34:35], 1.0 op_sel_hi:[1,0]
	v_and_b32_e32 v31, 0xffff0000, v31
	v_and_b32_e32 v30, 0xffff0000, v30
	v_pk_mul_f32 v[30:31], v[54:55], v[30:31]
	v_rcp_f32_e32 v35, v35
	s_nop 0
	v_mul_f32_e32 v35, v61, v35
	s_mov_b64 s[4:5], 0
	v_rcp_f32_e32 v34, v34
	s_nop 0
	v_mul_f32_e32 v34, v62, v34
	v_pk_mul_f32 v[30:31], v[34:35], v[30:31]
	v_cvt_pk_bf16_f32 v32, 0, v32
	v_cvt_pk_bf16_f32 v33, 0, v33
	v_cvt_pk_bf16_f32 v31, 0, v31
	v_cvt_pk_bf16_f32 v30, 0, v30
	v_and_b32_e32 v31, 0xffff0000, v31
	v_and_b32_e32 v30, 0xffff0000, v30
	v_or_b32_sdwa v31, v31, v33 dst_sel:DWORD dst_unused:UNUSED_PAD src0_sel:DWORD src1_sel:WORD_1
	v_or_b32_sdwa v30, v30, v32 dst_sel:DWORD dst_unused:UNUSED_PAD src0_sel:DWORD src1_sel:WORD_1
	global_store_dwordx4 v[50:51], v[28:31], off
	global_store_dwordx4 v[48:49], v[24:27], off
	global_store_dwordx4 v[46:47], v[20:23], off
	global_store_dwordx4 v[44:45], v[16:19], off
	global_store_dwordx4 v[42:43], v[12:15], off
	global_store_dwordx4 v[40:41], v[8:11], off
	global_store_dwordx4 v[38:39], v[4:7], off
	global_store_dwordx4 v[36:37], v[0:3], off
	s_barrier

; template <int DH, int MODE>
; __device__ void attn_item(const Params& p, int layer, int b, int blk, int head, char* smem) {
;     ...
;     V_SCATTER_(vr0, 0);
;     V_SCATTER_(vr1, 1);
;     if (KCH > 2) {
;       V_SCATTER_(vr2, 2);
;       V_SCATTER_(vr3, 3);
;     }
;     KV_LOAD_(it + 1);
;     if (!wskip) {
;       float4* s4 = reinterpret_cast<float4*>(Sf + row * SSTR + half * 32);
;       char* prow = Pb + half * 8192 + row * 64;
;       if (MODE == 0) {
;         const int kjb = kj0 + half * 32;
;         float tmax = -1e30f;
; #pragma unroll
;         for (int c = 0; c < 8; ++c) {
;           float4 v = s4[c];
;           float e[4] = {v.x, v.y, v.z, v.w};
; #pragma unroll
;           for (int k = 0; k < 4; ++k) {
;             int kj = kjb + c * 4 + k;
;             bool valid = (kj > row) && (kj <= row + 128);
;             tmax = valid ? fmaxf(tmax, e[k]) : tmax;
;           }
;         }
.LBB0_166:
	s_or_b64 exec, exec, s[6:7]
	s_add_i32 s86, s86, 1
	s_min_i32 s6, s86, s84
	s_add_i32 s6, s6, s83
	s_lshl_b32 s6, s6, 6
	s_add_i32 s6, s6, s85
	s_ashr_i32 s7, s6, 31
	s_add_u32 s6, s6, s81
	s_addc_u32 s7, s7, 0
	s_waitcnt lgkmcnt(0)
	s_barrier
	ds_write_b16 v96, v48
	ds_write_b16_d16_hi v96, v48 offset:64
	ds_write_b16 v96, v49 offset:128
	ds_write_b16_d16_hi v96, v49 offset:192
	ds_write_b16 v96, v50 offset:256
	ds_write_b16_d16_hi v96, v50 offset:320
	ds_write_b16 v96, v51 offset:384
	ds_write_b16_d16_hi v96, v51 offset:448
	s_waitcnt vmcnt(0)
	ds_write_b16 v96, v52 offset:2048
	ds_write_b16_d16_hi v96, v52 offset:2112
	ds_write_b16 v96, v53 offset:2176
	ds_write_b16_d16_hi v96, v53 offset:2240
	ds_write_b16 v96, v54 offset:2304
	ds_write_b16_d16_hi v96, v54 offset:2368
	ds_write_b16 v96, v55 offset:2432
	ds_write_b16_d16_hi v96, v55 offset:2496
	v_lshl_add_u64 v[48:49], s[6:7], 0, v[66:67]
	v_mad_u64_u32 v[52:53], s[10:11], v48, s55, v[76:77]
	v_or_b32_e32 v48, s6, v72
	v_mad_i32_i24 v53, v49, s55, v53
	v_mad_u64_u32 v[54:55], s[10:11], v48, s55, v[78:79]
	v_add_co_u32_e32 v48, vcc, 0x4c000, v52
	v_mad_i32_i24 v55, s7, v160, v55
	s_nop 0
	v_addc_co_u32_e32 v49, vcc, 0, v53, vcc
	global_load_dwordx4 v[60:63], v[48:49], off
	s_nop 0
	global_load_dwordx4 v[48:51], v[54:55], off
	global_load_dwordx4 v[56:59], v[52:53], off
	s_nop 0
	global_load_dwordx4 v[52:55], v[54:55], off offset:64
	s_and_saveexec_b64 s[52:53], s[50:51]
	s_cbranch_execz .LBB0_188
	v_add_u32_e32 v82, 0x4004, v90
	ds_read2_b32 v[82:83], v82 offset1:1
	ds_read_b32 v102, v90 offset:16396
	v_or_b32_e32 v101, s8, v89
	v_cmp_gt_i32_e32 vcc, v101, v74
	v_cmp_le_i32_e64 s[6:7], v101, v80
	s_and_b64 s[8:9], vcc, s[6:7]
	v_mov_b32_e32 v103, 0xf149f2ca
	s_and_saveexec_b64 s[6:7], s[8:9]
	s_cbranch_execz .LBB0_169
	ds_read_b32 v103, v90 offset:16384
	s_waitcnt lgkmcnt(0)
	v_max_f32_e32 v103, 0xf149f2ca, v103
.LBB0_169:
	s_or_b64 exec, exec, s[6:7]
	v_cmp_ge_i32_e32 vcc, v101, v74
	v_cmp_lt_i32_e64 s[6:7], v101, v80
	s_waitcnt lgkmcnt(1)
	v_max_f32_e32 v82, v103, v82
	s_and_b64 vcc, vcc, s[6:7]
	v_cndmask_b32_e32 v82, v103, v82, vcc
	v_or_b32_e32 v103, 2, v101
	v_cmp_gt_i32_e32 vcc, v103, v74
	v_cmp_le_i32_e64 s[6:7], v103, v80
	v_max_f32_e32 v83, v82, v83
	s_and_b64 vcc, vcc, s[6:7]
	v_cndmask_b32_e32 v82, v82, v83, vcc
	v_or_b32_e32 v83, 3, v101
	v_cmp_gt_i32_e32 vcc, v83, v74
	v_cmp_le_i32_e64 s[6:7], v83, v80
	s_waitcnt lgkmcnt(0)
	v_max_f32_e32 v83, v82, v102
	s_and_b64 vcc, vcc, s[6:7]
	v_cndmask_b32_e32 v103, v82, v83, vcc
	v_add_u32_e32 v82, 0x4014, v90
	ds_read2_b32 v[82:83], v82 offset1:1
	ds_read_b32 v102, v90 offset:16412
	v_or_b32_e32 v104, 4, v101
	v_cmp_gt_i32_e32 vcc, v104, v74
	v_cmp_le_i32_e64 s[6:7], v104, v80
	s_and_b64 s[8:9], vcc, s[6:7]
	s_and_saveexec_b64 s[6:7], s[8:9]
	s_cbranch_execz .LBB0_171
	ds_read_b32 v104, v90 offset:16400
	s_waitcnt lgkmcnt(0)
	v_max_f32_e32 v103, v103, v104
.LBB0_171:
	s_or_b64 exec, exec, s[6:7]
	v_or_b32_e32 v104, 5, v101
	v_cmp_gt_i32_e32 vcc, v104, v74
	v_cmp_le_i32_e64 s[6:7], v104, v80
	s_waitcnt lgkmcnt(1)
	v_max_f32_e32 v82, v103, v82
	s_and_b64 vcc, vcc, s[6:7]
	v_cndmask_b32_e32 v82, v103, v82, vcc
	v_or_b32_e32 v103, 6, v101
	v_cmp_gt_i32_e32 vcc, v103, v74
	v_cmp_le_i32_e64 s[6:7], v103, v80
	v_max_f32_e32 v83, v82, v83
	s_and_b64 vcc, vcc, s[6:7]
	v_cndmask_b32_e32 v82, v82, v83, vcc
	v_or_b32_e32 v83, 7, v101
	v_cmp_gt_i32_e32 vcc, v83, v74
	v_cmp_le_i32_e64 s[6:7], v83, v80
	s_waitcnt lgkmcnt(0)
	v_max_f32_e32 v83, v82, v102
	s_and_b64 vcc, vcc, s[6:7]
	v_cndmask_b32_e32 v103, v82, v83, vcc
	v_add_u32_e32 v82, 0x4024, v90
	ds_read2_b32 v[82:83], v82 offset1:1
	ds_read_b32 v102, v90 offset:16428
	v_or_b32_e32 v104, 8, v101
	v_cmp_gt_i32_e32 vcc, v104, v74
	v_cmp_le_i32_e64 s[6:7], v104, v80
	s_and_b64 s[8:9], vcc, s[6:7]
	s_and_saveexec_b64 s[6:7], s[8:9]
	s_cbranch_execz .LBB0_173
	ds_read_b32 v104, v90 offset:16416
	s_waitcnt lgkmcnt(0)
	v_max_f32_e32 v103, v103, v104
.LBB0_173:
	s_or_b64 exec, exec, s[6:7]
	v_or_b32_e32 v104, 9, v101
	v_cmp_gt_i32_e32 vcc, v104, v74
	v_cmp_le_i32_e64 s[6:7], v104, v80
	s_waitcnt lgkmcnt(1)
	v_max_f32_e32 v82, v103, v82
	s_and_b64 vcc, vcc, s[6:7]
	v_cndmask_b32_e32 v82, v103, v82, vcc
	v_or_b32_e32 v103, 10, v101
	v_cmp_gt_i32_e32 vcc, v103, v74
	v_cmp_le_i32_e64 s[6:7], v103, v80
	v_max_f32_e32 v83, v82, v83
	s_and_b64 vcc, vcc, s[6:7]
	v_cndmask_b32_e32 v82, v82, v83, vcc
	v_or_b32_e32 v83, 11, v101
	v_cmp_gt_i32_e32 vcc, v83, v74
	v_cmp_le_i32_e64 s[6:7], v83, v80
	s_waitcnt lgkmcnt(0)
	v_max_f32_e32 v83, v82, v102
	s_and_b64 vcc, vcc, s[6:7]
	v_cndmask_b32_e32 v103, v82, v83, vcc
	v_add_u32_e32 v82, 0x4034, v90
	ds_read2_b32 v[82:83], v82 offset1:1
	ds_read_b32 v102, v90 offset:16444
	v_or_b32_e32 v104, 12, v101
	v_cmp_gt_i32_e32 vcc, v104, v74
	v_cmp_le_i32_e64 s[6:7], v104, v80
	s_and_b64 s[8:9], vcc, s[6:7]
	s_and_saveexec_b64 s[6:7], s[8:9]
	s_cbranch_execz .LBB0_175
	ds_read_b32 v104, v90 offset:16432
	s_waitcnt lgkmcnt(0)
	v_max_f32_e32 v103, v103, v104
.LBB0_175:
	s_or_b64 exec, exec, s[6:7]
	v_or_b32_e32 v104, 13, v101
	v_cmp_gt_i32_e32 vcc, v104, v74
	v_cmp_le_i32_e64 s[6:7], v104, v80
	s_waitcnt lgkmcnt(1)
	v_max_f32_e32 v82, v103, v82
	s_and_b64 vcc, vcc, s[6:7]
	v_cndmask_b32_e32 v82, v103, v82, vcc
	v_or_b32_e32 v103, 14, v101
	v_cmp_gt_i32_e32 vcc, v103, v74
	v_cmp_le_i32_e64 s[6:7], v103, v80
	v_max_f32_e32 v83, v82, v83
	s_and_b64 vcc, vcc, s[6:7]
	v_cndmask_b32_e32 v82, v82, v83, vcc
	v_or_b32_e32 v83, 15, v101
	v_cmp_gt_i32_e32 vcc, v83, v74
	v_cmp_le_i32_e64 s[6:7], v83, v80
	s_waitcnt lgkmcnt(0)
	v_max_f32_e32 v83, v82, v102
	s_and_b64 vcc, vcc, s[6:7]
	v_cndmask_b32_e32 v103, v82, v83, vcc
	v_add_u32_e32 v82, 0x4044, v90
	ds_read2_b32 v[82:83], v82 offset1:1
	ds_read_b32 v102, v90 offset:16460
	v_or_b32_e32 v104, 16, v101
	v_cmp_gt_i32_e32 vcc, v104, v74
	v_cmp_le_i32_e64 s[6:7], v104, v80
	s_and_b64 s[8:9], vcc, s[6:7]
	s_and_saveexec_b64 s[6:7], s[8:9]
	s_cbranch_execz .LBB0_177
	ds_read_b32 v104, v90 offset:16448
	s_waitcnt lgkmcnt(0)
	v_max_f32_e32 v103, v103, v104
; template <int DH, int MODE>
; __device__ void attn_item(const Params& p, int layer, int b, int blk, int head, char* smem) {
;     ...
; #pragma unroll
;         for (int c = 0; c < 8; ++c) {
;           float4 v = s4[c];
;           float e[4] = {v.x, v.y, v.z, v.w};
; #pragma unroll
;           for (int k = 0; k < 4; ++k) {
;             int kj = kjb + c * 4 + k;
;             bool valid = (kj > row) && (kj <= row + 128);
;             tmax = valid ? fmaxf(tmax, e[k]) : tmax;
;           }
;         }
;         tmax = fmaxf(tmax, __shfl_xor(tmax, 1));
;         float m_new = fmaxf(m_run, tmax);
.LBB0_177:
	s_or_b64 exec, exec, s[6:7]
	v_or_b32_e32 v104, 17, v101
	v_cmp_gt_i32_e32 vcc, v104, v74
	v_cmp_le_i32_e64 s[6:7], v104, v80
	s_waitcnt lgkmcnt(1)
	v_max_f32_e32 v82, v103, v82
	s_and_b64 vcc, vcc, s[6:7]
	v_cndmask_b32_e32 v82, v103, v82, vcc
	v_or_b32_e32 v103, 18, v101
	v_cmp_gt_i32_e32 vcc, v103, v74
	v_cmp_le_i32_e64 s[6:7], v103, v80
	v_max_f32_e32 v83, v82, v83
	s_and_b64 vcc, vcc, s[6:7]
	v_cndmask_b32_e32 v82, v82, v83, vcc
	v_or_b32_e32 v83, 19, v101
	v_cmp_gt_i32_e32 vcc, v83, v74
	v_cmp_le_i32_e64 s[6:7], v83, v80
	s_waitcnt lgkmcnt(0)
	v_max_f32_e32 v83, v82, v102
	s_and_b64 vcc, vcc, s[6:7]
	v_cndmask_b32_e32 v103, v82, v83, vcc
	v_add_u32_e32 v82, 0x4054, v90
	ds_read2_b32 v[82:83], v82 offset1:1
	ds_read_b32 v102, v90 offset:16476
	v_or_b32_e32 v104, 20, v101
	v_cmp_gt_i32_e32 vcc, v104, v74
	v_cmp_le_i32_e64 s[6:7], v104, v80
	s_and_b64 s[8:9], vcc, s[6:7]
	s_and_saveexec_b64 s[6:7], s[8:9]
	s_cbranch_execz .LBB0_179
	ds_read_b32 v104, v90 offset:16464
	s_waitcnt lgkmcnt(0)
	v_max_f32_e32 v103, v103, v104
.LBB0_179:
	s_or_b64 exec, exec, s[6:7]
	v_or_b32_e32 v104, 21, v101
	v_cmp_gt_i32_e32 vcc, v104, v74
	v_cmp_le_i32_e64 s[6:7], v104, v80
	s_waitcnt lgkmcnt(1)
	v_max_f32_e32 v82, v103, v82
	s_and_b64 vcc, vcc, s[6:7]
	v_cndmask_b32_e32 v82, v103, v82, vcc
	v_or_b32_e32 v103, 22, v101
	v_cmp_gt_i32_e32 vcc, v103, v74
	v_cmp_le_i32_e64 s[6:7], v103, v80
	v_max_f32_e32 v83, v82, v83
	s_and_b64 vcc, vcc, s[6:7]
	v_cndmask_b32_e32 v82, v82, v83, vcc
	v_or_b32_e32 v83, 23, v101
	v_cmp_gt_i32_e32 vcc, v83, v74
	v_cmp_le_i32_e64 s[6:7], v83, v80
	s_waitcnt lgkmcnt(0)
	v_max_f32_e32 v83, v82, v102
	s_and_b64 vcc, vcc, s[6:7]
	v_cndmask_b32_e32 v103, v82, v83, vcc
	v_add_u32_e32 v82, 0x4064, v90
	ds_read2_b32 v[82:83], v82 offset1:1
	ds_read_b32 v102, v90 offset:16492
	v_or_b32_e32 v104, 24, v101
	v_cmp_gt_i32_e32 vcc, v104, v74
	v_cmp_le_i32_e64 s[6:7], v104, v80
	s_and_b64 s[8:9], vcc, s[6:7]
	s_and_saveexec_b64 s[6:7], s[8:9]
	s_cbranch_execz .LBB0_181
	ds_read_b32 v104, v90 offset:16480
	s_waitcnt lgkmcnt(0)
	v_max_f32_e32 v103, v103, v104
.LBB0_181:
	s_or_b64 exec, exec, s[6:7]
	v_or_b32_e32 v104, 25, v101
	v_cmp_gt_i32_e32 vcc, v104, v74
	v_cmp_le_i32_e64 s[6:7], v104, v80
	s_waitcnt lgkmcnt(1)
	v_max_f32_e32 v82, v103, v82
	s_and_b64 vcc, vcc, s[6:7]
	v_cndmask_b32_e32 v82, v103, v82, vcc
	v_or_b32_e32 v103, 26, v101
	v_cmp_gt_i32_e32 vcc, v103, v74
	v_cmp_le_i32_e64 s[6:7], v103, v80
	v_max_f32_e32 v83, v82, v83
	s_and_b64 vcc, vcc, s[6:7]
	v_cndmask_b32_e32 v82, v82, v83, vcc
	v_or_b32_e32 v83, 27, v101
	v_cmp_gt_i32_e32 vcc, v83, v74
	v_cmp_le_i32_e64 s[6:7], v83, v80
	s_waitcnt lgkmcnt(0)
	v_max_f32_e32 v83, v82, v102
	s_and_b64 vcc, vcc, s[6:7]
	v_cndmask_b32_e32 v103, v82, v83, vcc
	v_add_u32_e32 v82, 0x4074, v90
	ds_read2_b32 v[82:83], v82 offset1:1
	ds_read_b32 v102, v90 offset:16508
	v_or_b32_e32 v104, 28, v101
	v_cmp_gt_i32_e32 vcc, v104, v74
	v_cmp_le_i32_e64 s[6:7], v104, v80
	s_and_b64 s[8:9], vcc, s[6:7]
	s_and_saveexec_b64 s[6:7], s[8:9]
	s_cbranch_execz .LBB0_183
	ds_read_b32 v104, v90 offset:16496
	s_waitcnt lgkmcnt(0)
	v_max_f32_e32 v103, v103, v104
.LBB0_183:
	s_or_b64 exec, exec, s[6:7]
	v_or_b32_e32 v104, 29, v101
	v_cmp_gt_i32_e32 vcc, v104, v74
	v_cmp_le_i32_e64 s[6:7], v104, v80
	s_waitcnt lgkmcnt(1)
	v_max_f32_e32 v82, v103, v82
	s_and_b64 vcc, vcc, s[6:7]
	v_cndmask_b32_e32 v82, v103, v82, vcc
	v_or_b32_e32 v103, 30, v101
	v_cmp_gt_i32_e32 vcc, v103, v74
	v_cmp_le_i32_e64 s[6:7], v103, v80
	v_max_f32_e32 v83, v82, v83
	s_and_b64 vcc, vcc, s[6:7]
	v_cndmask_b32_e32 v82, v82, v83, vcc
	v_or_b32_e32 v83, 31, v101
	v_cmp_gt_i32_e32 vcc, v83, v74
	v_cmp_le_i32_e64 s[6:7], v83, v80
	s_waitcnt lgkmcnt(0)
	v_max_f32_e32 v83, v82, v102
	s_and_b64 vcc, vcc, s[6:7]
	v_cndmask_b32_e32 v82, v82, v83, vcc
	v_cmp_lt_i32_e32 vcc, v157, v158
	s_mov_b32 s87, 0
	v_mov_b32_e32 v103, 0
	v_cndmask_b32_e32 v83, v156, v157, vcc
	v_lshlrev_b32_e32 v83, 2, v83
	ds_bpermute_b32 v101, v83, v82
	v_mov_b32_e32 v102, v91
	s_waitcnt lgkmcnt(0)
	v_max3_f32 v82, v87, v82, v101
	v_mov_b32_e32 v101, v93
; __device__ __forceinline__ unsigned pack2(float a, float b) { return (unsigned)f2bf(a) | ((unsigned)f2bf(b) << 16); }
; template <int DH, int MODE>
; __device__ void attn_item(const Params& p, int layer, int b, int blk, int head, char* smem) {
;     ...
;         float alpha = __builtin_amdgcn_exp2f(m_run - m_new);
;         float psum = 0.f;
; #pragma unroll 2
;         for (int s8 = 0; s8 < 4; ++s8) {
;           float4 va = s4[2 * s8], vb = s4[2 * s8 + 1];
;           float e[8] = {va.x, va.y, va.z, va.w, vb.x, vb.y, vb.z, vb.w};
;           float pv[8];
; #pragma unroll
;           for (int k = 0; k < 8; ++k) {
;             int kj = kjb + s8 * 8 + k;
;             bool valid = (kj > row) && (kj <= row + 128);
;             float pe = valid ? __builtin_amdgcn_exp2f(e[k] - m_new) : 0.f;
;             pv[k] = pe;
;             psum += pe;
;           }
;           uint4 ov;
;           ov.x = pack2(pv[0], pv[1]); ov.y = pack2(pv[2], pv[3]);
;           ov.z = pack2(pv[4], pv[5]); ov.w = pack2(pv[6], pv[7]);
;           *reinterpret_cast<uint4*>(prow + s8 * 16) = ov;
;         }
;         psum += __shfl_xor(psum, 1);
;         l_run = l_run * alpha + psum;
;         m_run = m_new;
;         if (half == 0) alpha_s[row] = alpha;
.LBB0_184:
	ds_read_b128 v[104:107], v102
	ds_read_b128 v[108:111], v102 offset:16
	v_add_u32_e32 v112, s87, v92
	v_add_u32_e32 v113, 2, v112
	v_cmp_gt_i32_e64 s[6:7], v112, v74
	s_waitcnt lgkmcnt(1)
	v_sub_f32_e32 v104, v104, v82
	v_exp_f32_e32 v104, v104
	v_sub_f32_e32 v106, v106, v82
	v_sub_f32_e32 v105, v105, v82
	v_exp_f32_e32 v106, v106
	v_exp_f32_e32 v105, v105
	v_sub_f32_e32 v107, v107, v82
	v_cmp_le_i32_e64 s[10:11], v112, v80
	v_exp_f32_e32 v107, v107
	v_cmp_gt_i32_e32 vcc, v113, v65
	v_cmp_le_i32_e64 s[8:9], v113, v69
	s_and_b64 s[6:7], s[6:7], s[10:11]
	v_add_u32_e32 v114, 3, v112
	s_and_b64 vcc, vcc, s[8:9]
	v_cndmask_b32_e64 v104, 0, v104, s[6:7]
	v_cmp_lt_i32_e64 s[6:7], v112, v80
	v_cmp_ge_i32_e64 s[10:11], v112, v74
	v_cndmask_b32_e32 v106, 0, v106, vcc
	v_cmp_lt_i32_e32 vcc, v74, v114
	v_cmp_ge_i32_e64 s[8:9], v80, v114
	s_and_b64 s[6:7], s[6:7], s[10:11]
	v_add_f32_e32 v103, v103, v104
	s_and_b64 vcc, vcc, s[8:9]
	v_cndmask_b32_e64 v105, 0, v105, s[6:7]
	v_cndmask_b32_e32 v107, 0, v107, vcc
	v_add_f32_e32 v103, v103, v105
	v_add_f32_e32 v103, v103, v106
	v_cvt_pk_bf16_f32 v106, 0, v106
	s_waitcnt lgkmcnt(0)
	v_sub_f32_e32 v108, v108, v82
	v_sub_f32_e32 v110, v110, v82
	v_add_f32_e32 v103, v103, v107
	v_cvt_pk_bf16_f32 v104, 0, v104
	v_cvt_pk_bf16_f32 v107, 0, v107
	v_exp_f32_e32 v108, v108
	v_exp_f32_e32 v110, v110
	v_cvt_pk_bf16_f32 v105, 0, v105
	v_and_b32_e32 v107, 0xffff0000, v107
	v_sub_f32_e32 v109, v109, v82
	v_sub_f32_e32 v111, v111, v82
	v_and_b32_e32 v113, 0xffff0000, v105
	v_or_b32_sdwa v105, v107, v106 dst_sel:DWORD dst_unused:UNUSED_PAD src0_sel:DWORD src1_sel:WORD_1
	v_or_b32_e32 v106, 6, v112
	v_or_b32_e32 v107, 4, v112
	v_exp_f32_e32 v109, v109
	v_exp_f32_e32 v111, v111
	v_cmp_gt_i32_e32 vcc, v107, v74
	v_cmp_gt_i32_e64 s[6:7], v106, v65
	v_cmp_le_i32_e64 s[8:9], v107, v80
	v_cmp_le_i32_e64 s[10:11], v106, v69
	s_and_b64 s[6:7], s[6:7], s[10:11]
	s_and_b64 vcc, vcc, s[8:9]
	v_or_b32_e32 v106, 7, v112
	v_or_b32_e32 v107, 5, v112
	v_cndmask_b32_e32 v108, 0, v108, vcc
	v_cndmask_b32_e64 v110, 0, v110, s[6:7]
	v_cmp_gt_i32_e32 vcc, v107, v74
	v_cmp_gt_i32_e64 s[6:7], v106, v65
	v_cmp_le_i32_e64 s[8:9], v107, v80
	v_cmp_le_i32_e64 s[10:11], v106, v69
	s_and_b64 s[6:7], s[6:7], s[10:11]
	s_and_b64 vcc, vcc, s[8:9]
	v_cndmask_b32_e32 v109, 0, v109, vcc
	v_cndmask_b32_e64 v111, 0, v111, s[6:7]
	v_or_b32_sdwa v104, v113, v104 dst_sel:DWORD dst_unused:UNUSED_PAD src0_sel:DWORD src1_sel:WORD_1
	v_cvt_pk_bf16_f32 v113, 0, v108
	v_cvt_pk_bf16_f32 v107, 0, v111
	v_cvt_pk_bf16_f32 v114, 0, v109
	v_cvt_pk_bf16_f32 v106, 0, v110
	v_and_b32_e32 v107, 0xffff0000, v107
	v_and_b32_e32 v114, 0xffff0000, v114
	v_add_f32_e32 v103, v103, v108
	v_or_b32_sdwa v107, v107, v106 dst_sel:DWORD dst_unused:UNUSED_PAD src0_sel:DWORD src1_sel:WORD_1
	v_or_b32_sdwa v106, v114, v113 dst_sel:DWORD dst_unused:UNUSED_PAD src0_sel:DWORD src1_sel:WORD_1
	v_add_f32_e32 v103, v103, v109
	v_add_f32_e32 v103, v103, v110
	ds_write_b128 v101, v[104:107]
	v_add_f32_e32 v103, v103, v111
	ds_read_b128 v[104:107], v102 offset:32
	ds_read_b128 v[108:111], v102 offset:48
	v_add_u32_e32 v113, 8, v112
	v_add_u32_e32 v114, 10, v112
	v_cmp_gt_i32_e64 s[6:7], v113, v74
	s_waitcnt lgkmcnt(1)
	v_sub_f32_e32 v104, v104, v82
	v_exp_f32_e32 v104, v104
	v_sub_f32_e32 v106, v106, v82
	v_sub_f32_e32 v105, v105, v82
	v_exp_f32_e32 v106, v106
	v_exp_f32_e32 v105, v105
	v_sub_f32_e32 v107, v107, v82
	v_cmp_le_i32_e64 s[10:11], v113, v80
	v_exp_f32_e32 v107, v107
	v_cmp_gt_i32_e32 vcc, v114, v65
	v_cmp_le_i32_e64 s[8:9], v114, v69
	s_and_b64 s[6:7], s[6:7], s[10:11]
	v_add_u32_e32 v112, 11, v112
	s_and_b64 vcc, vcc, s[8:9]
	v_cndmask_b32_e64 v104, 0, v104, s[6:7]
	v_cmp_lt_i32_e64 s[6:7], v113, v80
	v_cmp_ge_i32_e64 s[10:11], v113, v74
	v_cndmask_b32_e32 v106, 0, v106, vcc
	v_cmp_lt_i32_e32 vcc, v74, v112
	v_cmp_ge_i32_e64 s[8:9], v80, v112
	s_and_b64 s[6:7], s[6:7], s[10:11]
	v_add_f32_e32 v103, v103, v104
	s_and_b64 vcc, vcc, s[8:9]
	v_cndmask_b32_e64 v105, 0, v105, s[6:7]
	v_cndmask_b32_e32 v107, 0, v107, vcc
	v_add_f32_e32 v103, v103, v105
	v_add_f32_e32 v103, v103, v106
	v_cvt_pk_bf16_f32 v106, 0, v106
	s_waitcnt lgkmcnt(0)
	v_sub_f32_e32 v108, v108, v82
	v_sub_f32_e32 v110, v110, v82
	v_add_f32_e32 v103, v103, v107
	v_cvt_pk_bf16_f32 v104, 0, v104
	v_cvt_pk_bf16_f32 v107, 0, v107
	v_exp_f32_e32 v108, v108
	v_exp_f32_e32 v110, v110
	v_cvt_pk_bf16_f32 v105, 0, v105
	v_and_b32_e32 v107, 0xffff0000, v107
	v_sub_f32_e32 v109, v109, v82
	v_sub_f32_e32 v111, v111, v82
	v_and_b32_e32 v112, 0xffff0000, v105
	v_or_b32_sdwa v105, v107, v106 dst_sel:DWORD dst_unused:UNUSED_PAD src0_sel:DWORD src1_sel:WORD_1
	v_or_b32_e32 v106, 6, v113
	v_or_b32_e32 v107, 4, v113
	v_exp_f32_e32 v109, v109
	v_exp_f32_e32 v111, v111
	v_cmp_gt_i32_e32 vcc, v107, v74
	v_cmp_gt_i32_e64 s[6:7], v106, v65
	v_cmp_le_i32_e64 s[8:9], v107, v80
	v_cmp_le_i32_e64 s[10:11], v106, v69
	s_and_b64 s[6:7], s[6:7], s[10:11]
	s_and_b64 vcc, vcc, s[8:9]
	v_or_b32_e32 v106, 7, v113
	v_or_b32_e32 v107, 5, v113
	v_cndmask_b32_e32 v108, 0, v108, vcc
	v_cndmask_b32_e64 v110, 0, v110, s[6:7]
	v_cmp_gt_i32_e32 vcc, v107, v74
	v_cmp_gt_i32_e64 s[6:7], v106, v65
	v_cmp_le_i32_e64 s[8:9], v107, v80
	v_cmp_le_i32_e64 s[10:11], v106, v69
	s_and_b64 s[6:7], s[6:7], s[10:11]
	s_and_b64 vcc, vcc, s[8:9]
	v_cndmask_b32_e32 v109, 0, v109, vcc
	v_cndmask_b32_e64 v111, 0, v111, s[6:7]
	v_or_b32_sdwa v104, v112, v104 dst_sel:DWORD dst_unused:UNUSED_PAD src0_sel:DWORD src1_sel:WORD_1
	v_cvt_pk_bf16_f32 v112, 0, v108
	v_cvt_pk_bf16_f32 v107, 0, v111
	v_cvt_pk_bf16_f32 v113, 0, v109
	v_add_f32_e32 v103, v103, v108
	v_cvt_pk_bf16_f32 v106, 0, v110
	v_and_b32_e32 v107, 0xffff0000, v107
	v_and_b32_e32 v113, 0xffff0000, v113
	v_add_f32_e32 v103, v103, v109
	v_or_b32_sdwa v107, v107, v106 dst_sel:DWORD dst_unused:UNUSED_PAD src0_sel:DWORD src1_sel:WORD_1
	v_or_b32_sdwa v106, v113, v112 dst_sel:DWORD dst_unused:UNUSED_PAD src0_sel:DWORD src1_sel:WORD_1
	v_add_f32_e32 v103, v103, v110
	s_add_i32 s87, s87, 16
	v_add_f32_e32 v103, v103, v111
	ds_write_b128 v101, v[104:107] offset:16
	v_add_u32_e32 v102, 64, v102
	v_add_u32_e32 v101, 32, v101
	s_cmp_eq_u32 s87, 32
	s_cbranch_scc0 .LBB0_184
	v_sub_f32_e32 v101, v87, v82
	ds_bpermute_b32 v87, v83, v103
	v_exp_f32_e32 v83, v101
	s_and_saveexec_b64 s[6:7], s[4:5]
	ds_write_b32 v97, v83 offset:8192
	s_or_b64 exec, exec, s[6:7]
	s_waitcnt lgkmcnt(0)
	v_add_f32_e32 v101, v103, v87
	v_fmac_f32_e32 v101, v88, v83
	v_mov_b32_e32 v87, v82
	v_mov_b32_e32 v88, v101

; template <int DH, int MODE>
; __device__ void attn_item(const Params& p, int layer, int b, int blk, int head, char* smem) {
;     ...
;   if (MODE == 0 && half == 0) linv_s[row] = 1.f / l_run;
;   __syncthreads();
;   {
;     constexpr int OST = DH + 4;
;     constexpr int CPR = DH / 8;
;     constexpr int NCH = 128 * CPR / 256;
;     float* Of = reinterpret_cast<float*>(smem);
;     uint4 gt[NCH];
; #pragma unroll
;     for (int i = 0; i < NCH; ++i) {
;       int q = tid + 256 * i, r = q / CPR, c = (q % CPR) * 8;
;       gt[i] = *reinterpret_cast<const uint4*>(P + (tq0 + r) * NP + gcol + c);
;     }
;     float lis[2][4];
; #pragma unroll
;     for (int m = 0; m < 2; ++m)
; #pragma unroll
;       for (int j = 0; j < 4; ++j) lis[m][j] = (MODE == 0) ? linv_s[wid * 32 + m * 16 + fq * 4 + j] : 1.f;
;     if (MODE == 0) __syncthreads();
; #pragma unroll
;     for (int m = 0; m < 2; ++m)
; #pragma unroll
;       for (int j = 0; j < 4; ++j) {
;         int r = wid * 32 + m * 16 + fq * 4 + j;
; #pragma unroll
;         for (int n = 0; n < NDT; ++n) Of[r * OST + n * 16 + fr] = o[m][n][j] * lis[m][j];
;       }
.LBB0_190:
	v_readfirstlane_b32 s8, v85
	s_and_saveexec_b64 s[6:7], s[4:5]
	s_cbranch_execz .LBB0_192
	v_rcp_f32_e32 v32, v88
	v_lshlrev_b32_e32 v33, 2, v74
	ds_write_b32 v33, v32 offset:8704
.LBB0_192:
	s_or_b64 exec, exec, s[6:7]
	v_lshl_add_u64 v[44:45], v[66:67], 0, s[26:27]
	v_mov_b64_e32 v[46:47], s[48:49]
	v_mad_u64_u32 v[32:33], s[6:7], v44, s55, v[46:47]
	v_mad_i32_i24 v33, v45, s55, v33
	v_lshl_add_u64 v[36:37], v[32:33], 0, v[70:71]
	v_add_u32_e32 v32, 0x100, v81
	v_ashrrev_i32_e32 v33, 31, v32
	v_lshrrev_b32_e32 v33, 29, v33
	v_add_u32_e32 v33, v32, v33
	v_ashrrev_i32_e32 v86, 3, v33
	v_and_b32_e32 v33, -8, v33
	v_sub_u32_e32 v85, v32, v33
	v_lshlrev_b32_e32 v32, 3, v85
	v_ashrrev_i32_e32 v33, 31, v32
	s_waitcnt vmcnt(2)
	v_add_u32_e32 v48, 0x200, v81
	v_lshlrev_b64 v[90:91], 1, v[32:33]
	v_ashrrev_i32_e32 v32, 31, v48
	v_lshrrev_b32_e32 v32, 29, v32
	v_add_u32_e32 v32, v48, v32
	v_ashrrev_i32_e32 v92, 3, v32
	v_and_b32_e32 v49, -8, v32
	v_add_u32_e32 v32, 0x300, v81
	v_ashrrev_i32_e32 v33, 31, v32
	v_lshrrev_b32_e32 v33, 29, v33
	v_ashrrev_i32_e32 v87, 31, v86
	v_add_u32_e32 v33, v32, v33
	v_lshl_add_u64 v[88:89], v[86:87], 0, s[26:27]
	v_ashrrev_i32_e32 v94, 3, v33
	v_and_b32_e32 v33, -8, v33
	v_mad_u64_u32 v[34:35], s[6:7], v88, s55, v[46:47]
	v_sub_u32_e32 v87, v32, v33
	v_ashrrev_i32_e32 v95, 31, v94
	v_mad_i32_i24 v35, v89, s55, v35
	v_lshlrev_b32_e32 v32, 3, v87
	v_lshl_add_u64 v[40:41], v[94:95], 0, s[26:27]
	v_lshl_add_u64 v[38:39], v[34:35], 0, v[90:91]
	v_mad_u64_u32 v[34:35], s[6:7], v40, s55, v[46:47]
	v_ashrrev_i32_e32 v33, 31, v32
	v_mad_i32_i24 v35, v41, s55, v35
	v_lshlrev_b64 v[42:43], 1, v[32:33]
	v_lshl_add_u64 v[32:33], v[34:35], 0, v[42:43]
	v_add_co_u32_e32 v32, vcc, s37, v32
	s_waitcnt lgkmcnt(0)
	s_nop 0
	v_addc_co_u32_e32 v33, vcc, 0, v33, vcc
	s_barrier
	global_load_dwordx4 v[32:35], v[32:33], off offset:512
	v_sub_u32_e32 v95, v48, v49
	v_ashrrev_i32_e32 v93, 31, v92
	v_lshlrev_b32_e32 v48, 3, v95
	v_lshl_add_u64 v[96:97], v[92:93], 0, s[26:27]
	v_mad_u64_u32 v[46:47], s[6:7], v96, s55, v[46:47]
	v_ashrrev_i32_e32 v49, 31, v48
	v_mad_i32_i24 v47, v97, s55, v47
	v_lshlrev_b64 v[98:99], 1, v[48:49]
	v_lshl_add_u64 v[100:101], v[46:47], 0, v[98:99]
	v_lshl_or_b32 v46, v75, 7, v128
	ds_read_b128 v[60:63], v46 offset:8704
	ds_read_b128 v[80:83], v46 offset:8768
	s_ashr_i32 s5, s8, 31
	s_add_u32 s4, s28, s8
	s_addc_u32 s5, s29, s5
	s_lshl_b32 s6, s80, 1
	s_add_u32 s4, s4, s6
	v_lshl_or_b32 v46, v84, 2, v64
	s_waitcnt lgkmcnt(0)
	v_mul_f32_e32 v69, v0, v80
	s_addc_u32 s5, s5, 0
	v_mul_lo_u32 v0, v66, s71
	v_mul_lo_u32 v46, v46, s71
	v_mul_f32_e32 v75, v1, v81
	v_lshl_add_u32 v66, v68, 2, v0
	v_mov_b64_e32 v[0:1], s[4:5]
	v_lshl_add_u32 v47, v73, 2, v46
	v_mul_f32_e32 v48, v16, v60
	v_mul_f32_e32 v49, v28, v60
	v_mul_f32_e32 v50, v24, v60
	v_mul_f32_e32 v51, v20, v60
	s_waitcnt vmcnt(1)
	v_mul_f32_e32 v52, v17, v61
	v_mul_f32_e32 v53, v29, v61
	v_mul_f32_e32 v54, v25, v61
	v_mul_f32_e32 v55, v21, v61
	v_mul_f32_e32 v56, v18, v62
	v_mul_f32_e32 v57, v30, v62
	v_mul_f32_e32 v58, v26, v62
	v_mul_f32_e32 v59, v22, v62
	v_mul_f32_e32 v60, v19, v63
	v_mul_f32_e32 v61, v31, v63
	v_mul_f32_e32 v62, v27, v63
	v_mul_f32_e32 v64, v23, v63
	v_mul_f32_e32 v63, v12, v80
	v_mul_f32_e32 v65, v8, v80
	v_mul_f32_e32 v67, v4, v80
	v_mul_f32_e32 v72, v13, v81
	v_mul_f32_e32 v73, v9, v81
	v_mul_f32_e32 v74, v5, v81
	v_mul_f32_e32 v76, v14, v82
	v_mul_f32_e32 v77, v10, v82
	v_mul_f32_e32 v78, v6, v82
	v_mul_f32_e32 v80, v2, v82
	v_mul_f32_e32 v79, v15, v83
	v_mul_f32_e32 v81, v11, v83
	v_mul_f32_e32 v82, v7, v83
	v_mul_f32_e32 v83, v3, v83
	v_mad_u64_u32 v[2:3], s[4:5], v44, s68, v[0:1]
	v_mad_i32_i24 v3, v45, s68, v3
	v_lshl_add_u64 v[12:13], v[2:3], 0, v[70:71]
	v_mul_lo_u32 v2, v86, s71
	v_lshl_add_u32 v46, v85, 5, v2
	v_mad_u64_u32 v[2:3], s[4:5], v88, s68, v[0:1]
	v_mad_i32_i24 v3, v89, s68, v3
	v_mad_u64_u32 v[4:5], s[4:5], v40, s68, v[0:1]
	v_lshl_add_u64 v[10:11], v[2:3], 0, v[90:91]
	v_mul_lo_u32 v2, v92, s71
	v_mad_i32_i24 v5, v41, s68, v5
	v_lshl_add_u32 v45, v95, 5, v2
	v_mad_u64_u32 v[2:3], s[4:5], v96, s68, v[0:1]
	v_lshl_add_u64 v[14:15], v[4:5], 0, v[42:43]
	v_mad_i32_i24 v3, v97, s68, v3
	v_add_co_u32_e32 v0, vcc, s37, v100
	v_lshl_add_u64 v[8:9], v[2:3], 0, v[98:99]
	v_mul_lo_u32 v2, v94, s71
	s_waitcnt vmcnt(0)
	v_lshlrev_b32_e32 v16, 16, v33
	v_lshlrev_b32_e32 v18, 16, v32
	v_mul_f32_e32 v6, 0xbfb8aa3b, v18
	v_mul_f32_e32 v7, 0xbfb8aa3b, v16
	v_exp_f32_e32 v6, v6
	v_exp_f32_e32 v7, v7
	v_addc_co_u32_e32 v1, vcc, 0, v101, vcc
	v_lshl_add_u32 v44, v87, 5, v2
	v_pk_add_f32 v[4:5], v[6:7], 1.0 op_sel_hi:[1,0]
	global_load_dwordx4 v[0:3], v[0:1], off offset:512
	v_and_b32_e32 v19, 0xffff0000, v33
	v_and_b32_e32 v20, 0xffff0000, v32
	v_mul_f32_e32 v6, 0xbfb8aa3b, v20
	v_rcp_f32_e32 v17, v5
	s_nop 0
	v_mul_f32_e32 v17, v16, v17
	v_mul_f32_e32 v7, 0xbfb8aa3b, v19
	v_exp_f32_e32 v6, v6
	v_exp_f32_e32 v7, v7
	s_nop 0
	v_pk_add_f32 v[6:7], v[6:7], 1.0 op_sel_hi:[1,0]
	v_rcp_f32_e32 v16, v4
	s_nop 0
	v_mul_f32_e32 v16, v18, v16
	v_lshlrev_b32_e32 v23, 16, v34
	v_rcp_f32_e32 v4, v7
	s_nop 0
	v_mul_f32_e32 v19, v19, v4
	v_lshlrev_b32_e32 v22, 16, v35
	v_mul_f32_e32 v4, 0xbfb8aa3b, v23
	v_mul_f32_e32 v5, 0xbfb8aa3b, v22
	v_exp_f32_e32 v4, v4
	v_exp_f32_e32 v5, v5
	v_rcp_f32_e32 v18, v6
	s_nop 0
	v_mul_f32_e32 v18, v20, v18
	v_and_b32_e32 v24, 0xffff0000, v35
	v_pk_add_f32 v[4:5], v[4:5], 1.0 op_sel_hi:[1,0]
	v_and_b32_e32 v25, 0xffff0000, v34
	v_mul_f32_e32 v6, 0xbfb8aa3b, v25
	v_exp_f32_e32 v6, v6
	v_rcp_f32_e32 v21, v5
	s_nop 0
	v_mul_f32_e32 v21, v22, v21
	v_mul_f32_e32 v7, 0xbfb8aa3b, v24
	v_exp_f32_e32 v7, v7
	s_nop 0
	v_pk_add_f32 v[6:7], v[6:7], 1.0 op_sel_hi:[1,0]
	v_rcp_f32_e32 v20, v4
	s_nop 0
	v_mul_f32_e32 v20, v23, v20
	v_rcp_f32_e32 v23, v7
	s_nop 0
	v_mul_f32_e32 v23, v24, v23
	s_waitcnt vmcnt(0)
; __device__ __forceinline__ unsigned pack2(float a, float b) { return (unsigned)f2bf(a) | ((unsigned)f2bf(b) << 16); }
; __device__ __forceinline__ float bflo(unsigned w) { return __uint_as_float(w << 16); }
; __device__ __forceinline__ float bfhi(unsigned w) { return __uint_as_float(w & 0xffff0000u); }
; __device__ __forceinline__ float silu_f(float g) { return g / (1.f + __expf(-g)); }
; template <int DH, int MODE>
; __device__ void attn_item(const Params& p, int layer, int b, int blk, int head, char* smem) {
;     ...
; #pragma unroll
;     for (int m = 0; m < 2; ++m)
; #pragma unroll
;       for (int j = 0; j < 4; ++j) {
;         int r = wid * 32 + m * 16 + fq * 4 + j;
; #pragma unroll
;         for (int n = 0; n < NDT; ++n) Of[r * OST + n * 16 + fr] = o[m][n][j] * lis[m][j];
;       }
;     __syncthreads();
; #pragma unroll
;     for (int i = 0; i < NCH; ++i) {
;       int q = tid + 256 * i, r = q / CPR, c = (q % CPR) * 8;
;       float4 m0 = *reinterpret_cast<const float4*>(Of + r * OST + c);
;       float4 m1 = *reinterpret_cast<const float4*>(Of + r * OST + c + 4);
;       float mm[8] = {m0.x, m0.y, m0.z, m0.w, m1.x, m1.y, m1.z, m1.w};
;       unsigned gw[4] = {gt[i].x, gt[i].y, gt[i].z, gt[i].w};
;       unsigned ow[4];
; #pragma unroll
;       for (int e = 0; e < 4; ++e)
;         ow[e] = pack2(mm[2 * e] * silu_f(bflo(gw[e])), mm[2 * e + 1] * silu_f(bfhi(gw[e])));
	v_lshlrev_b32_e32 v24, 16, v1
	v_lshlrev_b32_e32 v26, 16, v0
	v_mul_f32_e32 v4, 0xbfb8aa3b, v26
	v_mul_f32_e32 v5, 0xbfb8aa3b, v24
	v_exp_f32_e32 v4, v4
	v_exp_f32_e32 v5, v5
	v_and_b32_e32 v27, 0xffff0000, v1
	v_rcp_f32_e32 v22, v6
	s_nop 0
	v_mul_f32_e32 v22, v25, v22
	v_pk_add_f32 v[4:5], v[4:5], 1.0 op_sel_hi:[1,0]
	v_and_b32_e32 v28, 0xffff0000, v0
	v_mul_f32_e32 v0, 0xbfb8aa3b, v28
	v_exp_f32_e32 v6, v0
	v_lshlrev_b32_e32 v32, 16, v3
	v_mul_f32_e32 v7, 0xbfb8aa3b, v27
	v_rcp_f32_e32 v1, v5
	s_nop 0
	v_mul_f32_e32 v1, v24, v1
	v_exp_f32_e32 v7, v7
	s_nop 0
	v_pk_add_f32 v[24:25], v[6:7], 1.0 op_sel_hi:[1,0]
	v_rcp_f32_e32 v0, v4
	s_nop 0
	v_mul_f32_e32 v0, v26, v0
	v_lshlrev_b32_e32 v33, 16, v2
	v_rcp_f32_e32 v25, v25
	s_nop 0
	v_mul_f32_e32 v25, v27, v25
	v_add_co_u32_e64 v4, s[4:5], s37, v38
	s_nop 0
	s_nop 0
	v_addc_co_u32_e64 v5, s[4:5], 0, v39, s[4:5]
	global_load_dwordx4 v[4:7], v[4:5], off offset:512
	v_mul_f32_e32 v26, 0xbfb8aa3b, v33
	v_mul_f32_e32 v27, 0xbfb8aa3b, v32
	v_exp_f32_e32 v26, v26
	v_exp_f32_e32 v27, v27
	v_and_b32_e32 v30, 0xffff0000, v3
	v_rcp_f32_e32 v24, v24
	s_nop 0
	v_mul_f32_e32 v24, v28, v24
	v_pk_add_f32 v[26:27], v[26:27], 1.0 op_sel_hi:[1,0]
	v_and_b32_e32 v38, 0xffff0000, v2
	v_mul_f32_e32 v2, 0xbfb8aa3b, v38
	v_exp_f32_e32 v28, v2
	v_mul_f32_e32 v29, 0xbfb8aa3b, v30
	v_exp_f32_e32 v29, v29
	v_rcp_f32_e32 v3, v27
	s_nop 0
	v_mul_f32_e32 v3, v32, v3
	v_pk_add_f32 v[28:29], v[28:29], 1.0 op_sel_hi:[1,0]
	v_rcp_f32_e32 v2, v26
	s_nop 0
	v_mul_f32_e32 v2, v33, v2
	v_rcp_f32_e32 v27, v29
	s_nop 0
	v_mul_f32_e32 v27, v30, v27
	v_add_co_u32_e64 v30, s[4:5], s37, v36
	s_nop 0
	s_nop 0
	v_addc_co_u32_e64 v31, s[4:5], 0, v37, s[4:5]
	global_load_dwordx4 v[32:35], v[30:31], off offset:512
	v_rcp_f32_e32 v26, v28
	s_nop 0
	v_mul_f32_e32 v26, v38, v26
	s_barrier
	s_waitcnt vmcnt(1)
	v_lshlrev_b32_e32 v36, 16, v5
	v_lshlrev_b32_e32 v37, 16, v4
	v_mul_f32_e32 v30, 0xbfb8aa3b, v37
	v_mul_f32_e32 v31, 0xbfb8aa3b, v36
	v_exp_f32_e32 v30, v30
	v_exp_f32_e32 v31, v31
	v_and_b32_e32 v38, 0xffff0000, v5
	v_and_b32_e32 v39, 0xffff0000, v4
	v_mul_f32_e32 v4, 0xbfb8aa3b, v39
	v_pk_add_f32 v[28:29], v[30:31], 1.0 op_sel_hi:[1,0]
	v_exp_f32_e32 v30, v4
	ds_write2_b32 v47, v48, v49 offset1:16
	ds_write2_b32 v47, v50, v51 offset0:32 offset1:48
	ds_write2_b32 v47, v52, v53 offset0:68 offset1:84
	ds_write2_b32 v47, v54, v55 offset0:100 offset1:116
	ds_write2_b32 v47, v56, v57 offset0:136 offset1:152
	ds_write2_b32 v47, v58, v59 offset0:168 offset1:184
	ds_write2_b32 v47, v60, v61 offset0:204 offset1:220
	ds_write2_b32 v47, v62, v64 offset0:236 offset1:252
	v_mul_f32_e32 v31, 0xbfb8aa3b, v38
	v_exp_f32_e32 v31, v31
	v_rcp_f32_e32 v5, v29
	s_nop 0
	v_mul_f32_e32 v5, v36, v5
	v_pk_add_f32 v[30:31], v[30:31], 1.0 op_sel_hi:[1,0]
	v_rcp_f32_e32 v4, v28
	s_nop 0
	v_mul_f32_e32 v4, v37, v4
	v_rcp_f32_e32 v29, v31
	s_nop 0
	v_mul_f32_e32 v29, v38, v29
	v_lshlrev_b32_e32 v38, 16, v7
	v_lshlrev_b32_e32 v40, 16, v6
	v_mul_f32_e32 v36, 0xbfb8aa3b, v40
	v_mul_f32_e32 v37, 0xbfb8aa3b, v38
	v_exp_f32_e32 v36, v36
	v_exp_f32_e32 v37, v37
	v_rcp_f32_e32 v28, v30
	s_nop 0
	v_mul_f32_e32 v28, v39, v28
	v_and_b32_e32 v39, 0xffff0000, v7
	v_pk_add_f32 v[30:31], v[36:37], 1.0 op_sel_hi:[1,0]
	v_and_b32_e32 v41, 0xffff0000, v6
	v_mul_f32_e32 v6, 0xbfb8aa3b, v41
	v_exp_f32_e32 v36, v6
	v_mul_f32_e32 v37, 0xbfb8aa3b, v39
	v_exp_f32_e32 v37, v37
	v_rcp_f32_e32 v7, v31
	s_nop 0
	v_mul_f32_e32 v7, v38, v7
	v_pk_add_f32 v[36:37], v[36:37], 1.0 op_sel_hi:[1,0]
	v_rcp_f32_e32 v6, v30
	s_nop 0
	v_mul_f32_e32 v6, v40, v6
	v_rcp_f32_e32 v31, v37
	s_nop 0
	v_mul_f32_e32 v31, v39, v31
	s_waitcnt vmcnt(0)
	v_lshlrev_b32_e32 v42, 16, v33
	v_lshlrev_b32_e32 v43, 16, v32
	v_mul_f32_e32 v38, 0xbfb8aa3b, v43
	v_mul_f32_e32 v39, 0xbfb8aa3b, v42
	v_exp_f32_e32 v38, v38
	v_exp_f32_e32 v39, v39
	v_rcp_f32_e32 v30, v36
	s_nop 0
	v_mul_f32_e32 v30, v41, v30
	v_and_b32_e32 v68, 0xffff0000, v33
	v_pk_add_f32 v[36:37], v[38:39], 1.0 op_sel_hi:[1,0]
	v_and_b32_e32 v39, 0xffff0000, v32
	v_mul_f32_e32 v32, 0xbfb8aa3b, v39
	v_exp_f32_e32 v32, v32
	v_rcp_f32_e32 v41, v37
	s_nop 0
	v_mul_f32_e32 v41, v42, v41
	v_mul_f32_e32 v33, 0xbfb8aa3b, v68
	v_exp_f32_e32 v33, v33
	s_nop 0
	v_pk_add_f32 v[32:33], v[32:33], 1.0 op_sel_hi:[1,0]
	v_rcp_f32_e32 v40, v36
	s_nop 0
	v_mul_f32_e32 v40, v43, v40
	v_lshlrev_b32_e32 v70, 16, v34
	v_rcp_f32_e32 v43, v33
	s_nop 0
	v_mul_f32_e32 v43, v68, v43
	v_lshlrev_b32_e32 v38, 16, v35
	v_mul_f32_e32 v36, 0xbfb8aa3b, v70
	v_mul_f32_e32 v37, 0xbfb8aa3b, v38
	v_exp_f32_e32 v36, v36
	v_exp_f32_e32 v37, v37
	v_rcp_f32_e32 v42, v32
	s_nop 0
	v_mul_f32_e32 v42, v39, v42
	v_and_b32_e32 v39, 0xffff0000, v35
	v_pk_add_f32 v[32:33], v[36:37], 1.0 op_sel_hi:[1,0]
	v_and_b32_e32 v68, 0xffff0000, v34
	v_mul_f32_e32 v34, 0xbfb8aa3b, v68
	v_exp_f32_e32 v34, v34
	v_rcp_f32_e32 v71, v33
	s_nop 0
	v_mul_f32_e32 v71, v38, v71
	v_mul_f32_e32 v35, 0xbfb8aa3b, v39
	v_exp_f32_e32 v35, v35
	s_nop 0
	v_pk_add_f32 v[36:37], v[34:35], 1.0 op_sel_hi:[1,0]
	v_rcp_f32_e32 v33, v32
	s_nop 0
	v_mul_f32_e32 v70, v70, v33
	v_rcp_f32_e32 v85, v37
	s_nop 0
	v_mul_f32_e32 v85, v39, v85
	v_add_u32_e32 v32, 0x1000, v47
	ds_write2_b32 v32, v63, v65 offset0:64 offset1:80
	ds_write2_b32 v32, v67, v69 offset0:96 offset1:112
	ds_write2_b32 v32, v72, v73 offset0:132 offset1:148
	ds_write2_b32 v32, v74, v75 offset0:164 offset1:180
	ds_write2_b32 v32, v76, v77 offset0:200 offset1:216
	ds_write2_b32 v32, v78, v80 offset0:232 offset1:248
	v_add_u32_e32 v32, 0x1400, v47
	ds_write2_b32 v32, v79, v81 offset0:12 offset1:28
	ds_write2_b32 v32, v82, v83 offset0:44 offset1:60
	s_waitcnt lgkmcnt(0)
	s_barrier
; __device__ __forceinline__ unsigned pack2(float a, float b) { return (unsigned)f2bf(a) | ((unsigned)f2bf(b) << 16); }
; __device__ __forceinline__ float bflo(unsigned w) { return __uint_as_float(w << 16); }
; __device__ __forceinline__ float bfhi(unsigned w) { return __uint_as_float(w & 0xffff0000u); }
; __device__ __forceinline__ float silu_f(float g) { return g / (1.f + __expf(-g)); }
; template <int DH, int MODE>
; __device__ void attn_item(const Params& p, int layer, int b, int blk, int head, char* smem) {
;     ...
; #pragma unroll
;     for (int i = 0; i < NCH; ++i) {
;       int q = tid + 256 * i, r = q / CPR, c = (q % CPR) * 8;
;       float4 m0 = *reinterpret_cast<const float4*>(Of + r * OST + c);
;       float4 m1 = *reinterpret_cast<const float4*>(Of + r * OST + c + 4);
;       float mm[8] = {m0.x, m0.y, m0.z, m0.w, m1.x, m1.y, m1.z, m1.w};
;       unsigned gw[4] = {gt[i].x, gt[i].y, gt[i].z, gt[i].w};
;       unsigned ow[4];
; #pragma unroll
;       for (int e = 0; e < 4; ++e)
;         ow[e] = pack2(mm[2 * e] * silu_f(bflo(gw[e])), mm[2 * e + 1] * silu_f(bfhi(gw[e])));
;       *reinterpret_cast<uint4*>(Y + (tq0 + r) * YW + ycol + c) = make_uint4(ow[0], ow[1], ow[2], ow[3]);
;     }
;   }
;   __syncthreads();
	ds_read_b128 v[32:35], v66
	v_rcp_f32_e32 v84, v36
	s_nop 0
	v_mul_f32_e32 v84, v68, v84
	ds_read_b128 v[36:39], v66 offset:16
	v_add_co_u32_e32 v12, vcc, s74, v12
	s_waitcnt lgkmcnt(1)
	v_mov_b32_e32 v48, v32
	v_mov_b32_e32 v49, v34
	v_pk_mul_f32 v[40:41], v[40:41], v[48:49]
	v_mov_b32_e32 v34, v33
	v_pk_mul_f32 v[32:33], v[42:43], v[34:35]
	v_cvt_pk_bf16_f32 v35, 0, v40
	v_cvt_pk_bf16_f32 v34, 0, v41
	v_cvt_pk_bf16_f32 v33, 0, v33
	v_cvt_pk_bf16_f32 v32, 0, v32
	v_and_b32_e32 v33, 0xffff0000, v33
	v_and_b32_e32 v32, 0xffff0000, v32
	v_or_b32_sdwa v33, v33, v34 dst_sel:DWORD dst_unused:UNUSED_PAD src0_sel:DWORD src1_sel:WORD_1
	v_or_b32_sdwa v32, v32, v35 dst_sel:DWORD dst_unused:UNUSED_PAD src0_sel:DWORD src1_sel:WORD_1
	s_waitcnt lgkmcnt(0)
	v_mov_b32_e32 v34, v36
	v_mov_b32_e32 v35, v38
	v_pk_mul_f32 v[34:35], v[70:71], v[34:35]
	v_mov_b32_e32 v38, v37
	v_pk_mul_f32 v[36:37], v[84:85], v[38:39]
	v_cvt_pk_bf16_f32 v34, 0, v34
	v_cvt_pk_bf16_f32 v35, 0, v35
	v_cvt_pk_bf16_f32 v37, 0, v37
	v_cvt_pk_bf16_f32 v36, 0, v36
	v_and_b32_e32 v37, 0xffff0000, v37
	v_and_b32_e32 v36, 0xffff0000, v36
	v_or_b32_sdwa v35, v37, v35 dst_sel:DWORD dst_unused:UNUSED_PAD src0_sel:DWORD src1_sel:WORD_1
	v_or_b32_sdwa v34, v36, v34 dst_sel:DWORD dst_unused:UNUSED_PAD src0_sel:DWORD src1_sel:WORD_1
	ds_read_b128 v[36:39], v46
	v_addc_co_u32_e32 v13, vcc, 0, v13, vcc
	global_store_dwordx4 v[12:13], v[32:35], off offset:1024
	s_nop 0
	ds_read_b128 v[32:35], v46 offset:16
	s_waitcnt lgkmcnt(1)
	v_mov_b32_e32 v12, v36
	v_mov_b32_e32 v13, v38
	v_pk_mul_f32 v[4:5], v[4:5], v[12:13]
	v_mov_b32_e32 v38, v37
	v_pk_mul_f32 v[12:13], v[28:29], v[38:39]
	v_cvt_pk_bf16_f32 v4, 0, v4
	v_cvt_pk_bf16_f32 v5, 0, v5
	v_cvt_pk_bf16_f32 v13, 0, v13
	v_cvt_pk_bf16_f32 v12, 0, v12
	v_and_b32_e32 v13, 0xffff0000, v13
	v_and_b32_e32 v12, 0xffff0000, v12
	v_or_b32_sdwa v5, v13, v5 dst_sel:DWORD dst_unused:UNUSED_PAD src0_sel:DWORD src1_sel:WORD_1
	v_or_b32_sdwa v4, v12, v4 dst_sel:DWORD dst_unused:UNUSED_PAD src0_sel:DWORD src1_sel:WORD_1
	s_waitcnt lgkmcnt(0)
	v_mov_b32_e32 v12, v32
	v_mov_b32_e32 v13, v34
	v_pk_mul_f32 v[6:7], v[6:7], v[12:13]
	v_mov_b32_e32 v34, v33
	v_pk_mul_f32 v[12:13], v[30:31], v[34:35]
	v_cvt_pk_bf16_f32 v6, 0, v6
	v_cvt_pk_bf16_f32 v7, 0, v7
	v_cvt_pk_bf16_f32 v13, 0, v13
	v_cvt_pk_bf16_f32 v12, 0, v12
	ds_read_b128 v[28:31], v45
	v_and_b32_e32 v13, 0xffff0000, v13
	v_and_b32_e32 v12, 0xffff0000, v12
	v_add_co_u32_e32 v10, vcc, s74, v10
	v_or_b32_sdwa v7, v13, v7 dst_sel:DWORD dst_unused:UNUSED_PAD src0_sel:DWORD src1_sel:WORD_1
	v_or_b32_sdwa v6, v12, v6 dst_sel:DWORD dst_unused:UNUSED_PAD src0_sel:DWORD src1_sel:WORD_1
	v_addc_co_u32_e32 v11, vcc, 0, v11, vcc
	global_store_dwordx4 v[10:11], v[4:7], off offset:1024
	s_waitcnt lgkmcnt(0)
	v_mov_b32_e32 v10, v28
	v_mov_b32_e32 v11, v30
	ds_read_b128 v[4:7], v45 offset:16
	v_pk_mul_f32 v[0:1], v[0:1], v[10:11]
	v_mov_b32_e32 v30, v29
	v_pk_mul_f32 v[10:11], v[24:25], v[30:31]
	v_cvt_pk_bf16_f32 v0, 0, v0
	v_cvt_pk_bf16_f32 v1, 0, v1
	v_cvt_pk_bf16_f32 v11, 0, v11
	v_cvt_pk_bf16_f32 v10, 0, v10
	v_and_b32_e32 v11, 0xffff0000, v11
	v_and_b32_e32 v10, 0xffff0000, v10
	v_or_b32_sdwa v1, v11, v1 dst_sel:DWORD dst_unused:UNUSED_PAD src0_sel:DWORD src1_sel:WORD_1
	v_or_b32_sdwa v0, v10, v0 dst_sel:DWORD dst_unused:UNUSED_PAD src0_sel:DWORD src1_sel:WORD_1
	s_waitcnt lgkmcnt(0)
	v_mov_b32_e32 v10, v4
	v_mov_b32_e32 v11, v6
	v_pk_mul_f32 v[2:3], v[2:3], v[10:11]
	v_mov_b32_e32 v6, v5
	v_pk_mul_f32 v[4:5], v[26:27], v[6:7]
	v_cvt_pk_bf16_f32 v2, 0, v2
	v_cvt_pk_bf16_f32 v3, 0, v3
	v_cvt_pk_bf16_f32 v5, 0, v5
	v_cvt_pk_bf16_f32 v4, 0, v4
	v_and_b32_e32 v5, 0xffff0000, v5
	v_and_b32_e32 v4, 0xffff0000, v4
	v_or_b32_sdwa v3, v5, v3 dst_sel:DWORD dst_unused:UNUSED_PAD src0_sel:DWORD src1_sel:WORD_1
	v_or_b32_sdwa v2, v4, v2 dst_sel:DWORD dst_unused:UNUSED_PAD src0_sel:DWORD src1_sel:WORD_1
	ds_read_b128 v[4:7], v44
	v_add_co_u32_e32 v8, vcc, s74, v8
	s_nop 1
	v_addc_co_u32_e32 v9, vcc, 0, v9, vcc
	global_store_dwordx4 v[8:9], v[0:3], off offset:1024
	s_waitcnt lgkmcnt(0)
	v_mov_b32_e32 v8, v4
	v_mov_b32_e32 v9, v6
	ds_read_b128 v[0:3], v44 offset:16
	v_pk_mul_f32 v[8:9], v[16:17], v[8:9]
	v_mov_b32_e32 v6, v5
	v_pk_mul_f32 v[4:5], v[18:19], v[6:7]
	v_cvt_pk_bf16_f32 v7, 0, v8
	v_cvt_pk_bf16_f32 v6, 0, v9
	v_cvt_pk_bf16_f32 v5, 0, v5
	v_cvt_pk_bf16_f32 v4, 0, v4
	v_and_b32_e32 v5, 0xffff0000, v5
	v_and_b32_e32 v4, 0xffff0000, v4
	v_or_b32_sdwa v5, v5, v6 dst_sel:DWORD dst_unused:UNUSED_PAD src0_sel:DWORD src1_sel:WORD_1
	v_or_b32_sdwa v4, v4, v7 dst_sel:DWORD dst_unused:UNUSED_PAD src0_sel:DWORD src1_sel:WORD_1
	s_waitcnt lgkmcnt(0)
	v_mov_b32_e32 v6, v0
	v_mov_b32_e32 v7, v2
	v_pk_mul_f32 v[6:7], v[20:21], v[6:7]
	v_mov_b32_e32 v2, v1
	v_pk_mul_f32 v[0:1], v[22:23], v[2:3]
	v_cvt_pk_bf16_f32 v2, 0, v7
	v_cvt_pk_bf16_f32 v3, 0, v6
	v_cvt_pk_bf16_f32 v0, 0, v0
	v_cvt_pk_bf16_f32 v1, 0, v1
	v_and_b32_e32 v0, 0xffff0000, v0
	v_and_b32_e32 v1, 0xffff0000, v1
	v_or_b32_sdwa v6, v0, v3 dst_sel:DWORD dst_unused:UNUSED_PAD src0_sel:DWORD src1_sel:WORD_1
	v_add_co_u32_e32 v0, vcc, 0x184a1000, v14
	v_or_b32_sdwa v7, v1, v2 dst_sel:DWORD dst_unused:UNUSED_PAD src0_sel:DWORD src1_sel:WORD_1
	s_nop 0
	v_addc_co_u32_e32 v1, vcc, 0, v15, vcc
	global_store_dwordx4 v[0:1], v[4:7], off offset:1024
	s_barrier

; __device__ __forceinline__ unsigned pack2(float a, float b) { return (unsigned)f2bf(a) | ((unsigned)f2bf(b) << 16); }
; template <int DH, int MODE>
; __device__ void attn_item(const Params& p, int layer, int b, int blk, int head, char* smem) {
;     ...
;         for (int c = 7; c >= 0; --c) {
;           float4 v = s4[c];
;           float e[4] = {v.x, v.y, v.z, v.w};
; #pragma unroll
;           for (int k = 3; k >= 0; --k) {
;             float z = e[k];
;             bool valid = (kpb + c * 4 + k) < qpos;
;             float sp = fmaxf(z, 0.f) + __builtin_amdgcn_logf(1.f + __builtin_amdgcn_exp2f(-fabsf(z)));
;             run += valid ? -sp : 0.f;
;             e[k] = z + run;
;           }
;           s4[c] = make_float4(e[0], e[1], e[2], e[3]);
;         }
;         float other = __shfl_xor(run, 1);
;         float offs = m_run + (half == 0 ? other : 0.f);
; #pragma unroll 2
;         for (int s8 = 0; s8 < 4; ++s8) {
;           float4 va = s4[2 * s8], vb = s4[2 * s8 + 1];
;           float e[8] = {va.x, va.y, va.z, va.w, vb.x, vb.y, vb.z, vb.w};
;           float pv[8];
; #pragma unroll
;           for (int k = 0; k < 8; ++k) {
;             bool valid = (kpb + s8 * 8 + k) < qpos;
;             pv[k] = valid ? __builtin_amdgcn_exp2f(e[k] + offs) : 0.f;
;           }
;           uint4 ov;
;           ov.x = pack2(pv[0], pv[1]); ov.y = pack2(pv[2], pv[3]);
;           ov.z = pack2(pv[4], pv[5]); ov.w = pack2(pv[6], pv[7]);
;           *reinterpret_cast<uint4*>(prow + s8 * 16) = ov;
.LBB0_205:
	ds_read_b128 v[150:153], v148 offset:16
	ds_read_b128 v[176:179], v148
	v_add_u32_e32 v149, s52, v173
	v_add_u32_e32 v182, 0x3fdd, v149
	v_cmp_lt_i32_e32 vcc, v182, v144
	s_waitcnt lgkmcnt(1)
	v_exp_f32_e64 v175, -|v151|
	v_exp_f32_e64 v184, -|v150|
	v_max_f32_e32 v183, 0, v151
	v_add_f32_e32 v175, 1.0, v175
	v_log_f32_e32 v175, v175
	v_add_f32_e32 v182, 1.0, v184
	v_exp_f32_e64 v184, -|v153|
	v_add_u32_e32 v147, 0x3fdc, v149
	v_add_f32_e32 v175, v183, v175
	v_log_f32_e32 v182, v182
	v_cndmask_b32_e64 v175, 0, -v175, vcc
	v_cmp_lt_i32_e32 vcc, v147, v144
	v_add_f32_e32 v147, 1.0, v184
	v_exp_f32_e64 v184, -|v152|
	v_log_f32_e32 v147, v147
	v_max_f32_e32 v183, 0, v150
	v_add_u32_e32 v180, 0x3fdf, v149
	v_add_f32_e32 v182, v183, v182
	v_cndmask_b32_e64 v182, 0, -v182, vcc
	v_max_f32_e32 v183, 0, v153
	v_cmp_lt_i32_e32 vcc, v180, v144
	v_add_f32_e32 v180, 1.0, v184
	v_add_f32_e32 v147, v183, v147
	v_log_f32_e32 v180, v180
	v_cndmask_b32_e64 v147, 0, -v147, vcc
	v_add_f32_e32 v147, v146, v147
	v_add_u32_e32 v181, 0x3fde, v149
	v_max_f32_e32 v146, 0, v152
	v_add_f32_e32 v146, v146, v180
	v_cmp_lt_i32_e32 vcc, v181, v144
	s_add_i32 s52, s52, -8
	s_cmpk_eq_i32 s52, 0xffe0
	v_cndmask_b32_e64 v146, 0, -v146, vcc
	v_add_f32_e32 v146, v146, v147
	v_pk_add_f32 v[152:153], v[152:153], v[146:147]
	v_add_f32_e32 v147, v175, v146
	v_add_f32_e32 v146, v182, v147
	v_pk_add_f32 v[150:151], v[150:151], v[146:147]
	ds_write_b128 v148, v[150:153] offset:16
	s_waitcnt lgkmcnt(1)
	v_exp_f32_e64 v150, -|v177|
	v_exp_f32_e64 v175, -|v176|
	v_add_u32_e32 v147, 0x3fd8, v149
	v_add_f32_e32 v150, 1.0, v150
	v_log_f32_e32 v150, v150
	v_add_u32_e32 v151, 0x3fdb, v149
	v_add_u32_e32 v152, 0x3fda, v149
	v_add_u32_e32 v149, 0x3fd9, v149
	v_max_f32_e32 v153, 0, v177
	v_add_f32_e32 v150, v153, v150
	v_cmp_lt_i32_e32 vcc, v149, v144
	v_max_f32_e32 v153, 0, v176
	s_nop 0
	v_cndmask_b32_e64 v149, 0, -v150, vcc
	v_add_f32_e32 v150, 1.0, v175
	v_exp_f32_e64 v175, -|v179|
	v_log_f32_e32 v150, v150
	v_cmp_lt_i32_e32 vcc, v147, v144
	v_add_f32_e32 v147, 1.0, v175
	v_exp_f32_e64 v175, -|v178|
	v_log_f32_e32 v147, v147
	v_add_f32_e32 v150, v153, v150
	v_cndmask_b32_e64 v150, 0, -v150, vcc
	v_max_f32_e32 v153, 0, v179
	v_cmp_lt_i32_e32 vcc, v151, v144
	v_add_f32_e32 v151, 1.0, v175
	v_add_f32_e32 v147, v153, v147
	v_log_f32_e32 v151, v151
	v_cndmask_b32_e64 v147, 0, -v147, vcc
	v_add_f32_e32 v147, v146, v147
	v_max_f32_e32 v146, 0, v178
	v_add_f32_e32 v146, v146, v151
	v_cmp_lt_i32_e32 vcc, v152, v144
	s_nop 1
	v_cndmask_b32_e64 v146, 0, -v146, vcc
	v_add_f32_e32 v146, v146, v147
	v_pk_add_f32 v[152:153], v[178:179], v[146:147]
	v_add_f32_e32 v147, v149, v146
	v_add_f32_e32 v146, v150, v147
	v_pk_add_f32 v[150:151], v[176:177], v[146:147]
	ds_write_b128 v148, v[150:153]
	v_subrev_u32_e32 v148, 32, v148
	s_cbranch_scc0 .LBB0_205
	ds_bpermute_b32 v147, v163, v146
	s_mov_b32 s85, 0
	v_mov_b32_e32 v175, v168
	v_mov_b32_e32 v177, v167
	s_waitcnt lgkmcnt(0)
	v_cndmask_b32_e64 v148, 0, v147, s[6:7]
	v_add_f32_e32 v176, v174, v148
	s_branch .LBB0_208
.LBB0_207:
	s_or_b64 exec, exec, s[52:53]
	s_waitcnt lgkmcnt(3)
	v_add_f32_e32 v152, v176, v152
	v_exp_f32_e32 v152, v152
	s_waitcnt lgkmcnt(1)
	v_add_f32_e32 v149, v176, v149
	v_exp_f32_e32 v149, v149
	v_add_u32_e32 v182, 0x3fc9, v178
	v_add_f32_e32 v151, v176, v151
	v_add_f32_e32 v148, v176, v148
	v_cmp_lt_i32_e32 vcc, v182, v144
	v_exp_f32_e32 v185, v151
	v_exp_f32_e32 v186, v148
	v_add_u32_e32 v148, 0x3fce, v178
	s_waitcnt lgkmcnt(0)
	v_add_f32_e32 v151, v176, v180
	v_cndmask_b32_e32 v152, 0, v152, vcc
	v_exp_f32_e32 v151, v151
	v_cmp_lt_i32_e32 vcc, v148, v144
	v_add_u32_e32 v148, 0x3fcf, v178
	v_add_f32_e32 v153, v176, v153
	v_cndmask_b32_e32 v149, 0, v149, vcc
	v_cmp_lt_i32_e32 vcc, v148, v144
	v_cvt_pk_bf16_f32 v148, 0, v179
	v_exp_f32_e32 v153, v153
	v_lshrrev_b32_e32 v148, 16, v148
	v_cvt_pk_bf16_f32 v152, 0, v152
	v_add_f32_e32 v150, v176, v150
	v_cndmask_b32_e32 v151, 0, v151, vcc
	v_and_or_b32 v148, v152, s62, v148
	v_or_b32_e32 v182, 2, v181
	v_exp_f32_e32 v150, v150
	v_cvt_pk_bf16_f32 v149, 0, v149
	v_or_b32_e32 v183, 4, v181
	v_lshrrev_b32_e32 v149, 16, v149
	v_cvt_pk_bf16_f32 v151, 0, v151
	v_cmp_lt_i32_e32 vcc, v182, v144
	v_or_b32_e32 v184, 5, v181
	v_or_b32_e32 v181, 3, v181
	v_and_or_b32 v151, v151, s62, v149
	v_cndmask_b32_e32 v149, 0, v153, vcc
	v_cmp_lt_i32_e32 vcc, v183, v131
	v_cvt_pk_bf16_f32 v149, 0, v149
	s_nop 0
	v_cndmask_b32_e32 v152, 0, v185, vcc
	v_cmp_lt_i32_e32 vcc, v181, v144
	v_cvt_pk_bf16_f32 v152, 0, v152
	s_nop 0
	v_cndmask_b32_e32 v150, 0, v150, vcc
	v_cmp_lt_i32_e32 vcc, v184, v131
	v_cvt_pk_bf16_f32 v150, 0, v150
	s_nop 0
	v_cndmask_b32_e32 v153, 0, v186, vcc
	v_cvt_pk_bf16_f32 v153, 0, v153
	v_and_b32_e32 v153, 0xffff0000, v153
	v_and_b32_e32 v178, 0xffff0000, v150
	v_or_b32_sdwa v150, v153, v152 dst_sel:DWORD dst_unused:UNUSED_PAD src0_sel:DWORD src1_sel:WORD_1
	v_or_b32_sdwa v149, v178, v149 dst_sel:DWORD dst_unused:UNUSED_PAD src0_sel:DWORD src1_sel:WORD_1
	s_add_i32 s85, s85, 16
	ds_write_b128 v175, v[148:151] offset:16
	v_add_u32_e32 v177, 64, v177
	s_cmp_eq_u32 s85, 32
	v_add_u32_e32 v175, 32, v175
	s_cbranch_scc1 .LBB0_213

; __device__ __forceinline__ unsigned pack2(float a, float b) { return (unsigned)f2bf(a) | ((unsigned)f2bf(b) << 16); }
; template <int DH, int MODE>
; __device__ void attn_item(const Params& p, int layer, int b, int blk, int head, char* smem) {
;     ...
;         for (int s8 = 0; s8 < 4; ++s8) {
;           float4 va = s4[2 * s8], vb = s4[2 * s8 + 1];
;           float e[8] = {va.x, va.y, va.z, va.w, vb.x, vb.y, vb.z, vb.w};
;           float pv[8];
; #pragma unroll
;           for (int k = 0; k < 8; ++k) {
;             bool valid = (kpb + s8 * 8 + k) < qpos;
;             pv[k] = valid ? __builtin_amdgcn_exp2f(e[k] + offs) : 0.f;
;           }
;           uint4 ov;
;           ov.x = pack2(pv[0], pv[1]); ov.y = pack2(pv[2], pv[3]);
;           ov.z = pack2(pv[4], pv[5]); ov.w = pack2(pv[6], pv[7]);
;           *reinterpret_cast<uint4*>(prow + s8 * 16) = ov;
.LBB0_210:
	s_or_b64 exec, exec, s[52:53]
	s_waitcnt lgkmcnt(3)
	v_add_f32_e32 v152, v176, v152
	v_exp_f32_e32 v152, v152
	s_waitcnt lgkmcnt(1)
	v_add_f32_e32 v149, v176, v149
	v_exp_f32_e32 v149, v149
	v_add_u32_e32 v183, 0x3fc1, v178
	v_add_f32_e32 v151, v176, v151
	v_add_f32_e32 v148, v176, v148
	v_cmp_lt_i32_e32 vcc, v183, v144
	v_exp_f32_e32 v186, v151
	v_exp_f32_e32 v187, v148
	v_add_u32_e32 v148, 0x3fc6, v178
	s_waitcnt lgkmcnt(0)
	v_add_f32_e32 v151, v176, v180
	v_cndmask_b32_e32 v152, 0, v152, vcc
	v_exp_f32_e32 v151, v151
	v_cmp_lt_i32_e32 vcc, v148, v144
	v_add_u32_e32 v148, 0x3fc7, v178
	v_add_f32_e32 v153, v176, v153
	v_cndmask_b32_e32 v149, 0, v149, vcc
	v_cmp_lt_i32_e32 vcc, v148, v144
	v_cvt_pk_bf16_f32 v148, 0, v181
	v_exp_f32_e32 v153, v153
	v_lshrrev_b32_e32 v148, 16, v148
	v_cvt_pk_bf16_f32 v152, 0, v152
	v_add_f32_e32 v150, v176, v150
	v_cndmask_b32_e32 v151, 0, v151, vcc
	v_and_or_b32 v148, v152, s62, v148
	v_or_b32_e32 v183, 2, v182
	v_exp_f32_e32 v150, v150
	v_cvt_pk_bf16_f32 v149, 0, v149
	v_or_b32_e32 v184, 4, v182
	v_lshrrev_b32_e32 v149, 16, v149
	v_cvt_pk_bf16_f32 v151, 0, v151
	v_cmp_lt_i32_e32 vcc, v183, v144
	v_or_b32_e32 v185, 5, v182
	v_or_b32_e32 v182, 3, v182
	v_and_or_b32 v151, v151, s62, v149
	v_cndmask_b32_e32 v149, 0, v153, vcc
	v_cmp_lt_i32_e32 vcc, v184, v131
	v_cvt_pk_bf16_f32 v149, 0, v149
	s_nop 0
	v_cndmask_b32_e32 v152, 0, v186, vcc
	v_cmp_lt_i32_e32 vcc, v182, v144
	v_cvt_pk_bf16_f32 v152, 0, v152
	s_nop 0
	v_cndmask_b32_e32 v150, 0, v150, vcc
	v_cmp_lt_i32_e32 vcc, v185, v131
	v_cvt_pk_bf16_f32 v150, 0, v150
	s_nop 0
	v_cndmask_b32_e32 v153, 0, v187, vcc
	v_cvt_pk_bf16_f32 v153, 0, v153
	v_and_b32_e32 v153, 0xffff0000, v153
	v_and_b32_e32 v180, 0xffff0000, v150
	v_or_b32_sdwa v150, v153, v152 dst_sel:DWORD dst_unused:UNUSED_PAD src0_sel:DWORD src1_sel:WORD_1
	v_or_b32_sdwa v149, v180, v149 dst_sel:DWORD dst_unused:UNUSED_PAD src0_sel:DWORD src1_sel:WORD_1
	ds_write_b128 v175, v[148:151]
	ds_read2_b32 v[152:153], v177 offset0:9 offset1:10
	ds_read2_b32 v[150:151], v177 offset0:11 offset1:12
	ds_read2_b32 v[148:149], v177 offset0:13 offset1:14
	ds_read_b32 v180, v177 offset:60
	v_add_u32_e32 v181, 0x3fc8, v178
	v_cmp_lt_i32_e32 vcc, v181, v144
	s_and_saveexec_b64 s[52:53], vcc
	s_cbranch_execz .LBB0_207
	ds_read_b32 v179, v177 offset:32
	s_waitcnt lgkmcnt(0)
	v_add_f32_e32 v179, v176, v179
	v_exp_f32_e32 v179, v179
	s_branch .LBB0_207

; template <int WM, int WN>
; __device__ __forceinline__ void store_tile_bf16(const f32x4 (&acc)[WM][WN], u16* dst, int ld, char* smem) {
;   constexpr int BM = 32 * WM, BN = 32 * WN, STR = BN + 8;
;   const int tid = opaque_tid(), lane = tid & 63, wid = tid >> 6;
;   const int wr = wid >> 1, wc = wid & 1, fr = lane & 15, fq = lane >> 4;
;   u16* T = reinterpret_cast<u16*>(smem);
; #pragma unroll
;   for (int m = 0; m < WM; ++m)
; #pragma unroll
;     for (int n = 0; n < WN; ++n)
; #pragma unroll
;       for (int j = 0; j < 4; ++j)
;         T[(wr * 16 * WM + m * 16 + fq * 4 + j) * STR + wc * 16 * WN + n * 16 + fr] = f2bf(acc[m][n][j]);
;   __syncthreads();
.LBB0_257:
	v_mov_b32_e32 v1, v232
	s_waitcnt vmcnt(7)
	v_lshrrev_b32_e32 v3, 2, v1
	v_lshrrev_b32_e32 v2, 1, v1
	v_and_b32_e32 v3, 12, v3
	v_and_or_b32 v2, v2, s64, v3
	v_and_b32_e32 v3, 0x4f, v1
	v_mul_lo_u32 v2, v2, s65
	v_lshl_add_u32 v2, v3, 1, v2
	v_cvt_pk_bf16_f32 v3, 0, v65
	ds_write_b16_d16_hi v2, v3 offset:272
	v_cvt_pk_bf16_f32 v3, 0, v66
	ds_write_b16_d16_hi v2, v3 offset:544
	v_cvt_pk_bf16_f32 v3, 0, v67
	ds_write_b16_d16_hi v2, v3 offset:816
	v_cvt_pk_bf16_f32 v3, 0, v60
	ds_write_b16_d16_hi v2, v3 offset:32
	v_cvt_pk_bf16_f32 v3, 0, v61
	ds_write_b16_d16_hi v2, v3 offset:304
	v_cvt_pk_bf16_f32 v3, 0, v62
	ds_write_b16_d16_hi v2, v3 offset:576
	v_cvt_pk_bf16_f32 v3, 0, v63
	ds_write_b16_d16_hi v2, v3 offset:848
	v_cvt_pk_bf16_f32 v3, 0, v56
	ds_write_b16_d16_hi v2, v3 offset:64
	v_cvt_pk_bf16_f32 v3, 0, v57
	ds_write_b16_d16_hi v2, v3 offset:336
	v_cvt_pk_bf16_f32 v3, 0, v58
	ds_write_b16_d16_hi v2, v3 offset:608
	v_cvt_pk_bf16_f32 v3, 0, v59
	ds_write_b16_d16_hi v2, v3 offset:880
	v_cvt_pk_bf16_f32 v3, 0, v52
	ds_write_b16_d16_hi v2, v3 offset:96
	v_cvt_pk_bf16_f32 v3, 0, v53
	ds_write_b16_d16_hi v2, v3 offset:368
	v_cvt_pk_bf16_f32 v3, 0, v54
	ds_write_b16_d16_hi v2, v3 offset:640
	v_cvt_pk_bf16_f32 v3, 0, v55
	ds_write_b16_d16_hi v2, v3 offset:912
	v_cvt_pk_bf16_f32 v3, 0, v48
	ds_write_b16_d16_hi v2, v3 offset:4352
	v_cvt_pk_bf16_f32 v3, 0, v49
	ds_write_b16_d16_hi v2, v3 offset:4624
	v_cvt_pk_bf16_f32 v3, 0, v50
	ds_write_b16_d16_hi v2, v3 offset:4896
	v_cvt_pk_bf16_f32 v3, 0, v51
	ds_write_b16_d16_hi v2, v3 offset:5168
	v_cvt_pk_bf16_f32 v3, 0, v44
	ds_write_b16_d16_hi v2, v3 offset:4384
	v_cvt_pk_bf16_f32 v3, 0, v45
	ds_write_b16_d16_hi v2, v3 offset:4656
	v_cvt_pk_bf16_f32 v3, 0, v46
	ds_write_b16_d16_hi v2, v3 offset:4928
	v_cvt_pk_bf16_f32 v3, 0, v47
	ds_write_b16_d16_hi v2, v3 offset:5200
	v_cvt_pk_bf16_f32 v3, 0, v40
	ds_write_b16_d16_hi v2, v3 offset:4416
	v_cvt_pk_bf16_f32 v3, 0, v41
	ds_write_b16_d16_hi v2, v3 offset:4688
	v_cvt_pk_bf16_f32 v3, 0, v42
	ds_write_b16_d16_hi v2, v3 offset:4960
	v_cvt_pk_bf16_f32 v3, 0, v43
	ds_write_b16_d16_hi v2, v3 offset:5232
	v_cvt_pk_bf16_f32 v3, 0, v36
	ds_write_b16_d16_hi v2, v3 offset:4448
	v_cvt_pk_bf16_f32 v3, 0, v37
	ds_write_b16_d16_hi v2, v3 offset:4720
	v_cvt_pk_bf16_f32 v3, 0, v38
	ds_write_b16_d16_hi v2, v3 offset:4992
	v_cvt_pk_bf16_f32 v3, 0, v39
	ds_write_b16_d16_hi v2, v3 offset:5264
	v_cvt_pk_bf16_f32 v3, 0, v32
	ds_write_b16_d16_hi v2, v3 offset:8704
	v_cvt_pk_bf16_f32 v3, 0, v33
	ds_write_b16_d16_hi v2, v3 offset:8976
	v_cvt_pk_bf16_f32 v3, 0, v34
	ds_write_b16_d16_hi v2, v3 offset:9248
	v_cvt_pk_bf16_f32 v3, 0, v35
	ds_write_b16_d16_hi v2, v3 offset:9520
	v_cvt_pk_bf16_f32 v3, 0, v28
	ds_write_b16_d16_hi v2, v3 offset:8736
	v_cvt_pk_bf16_f32 v3, 0, v29
	ds_write_b16_d16_hi v2, v3 offset:9008
	v_cvt_pk_bf16_f32 v3, 0, v30
	ds_write_b16_d16_hi v2, v3 offset:9280
	v_cvt_pk_bf16_f32 v3, 0, v31
	ds_write_b16_d16_hi v2, v3 offset:9552
	v_cvt_pk_bf16_f32 v3, 0, v24
	ds_write_b16_d16_hi v2, v3 offset:8768
	v_cvt_pk_bf16_f32 v3, 0, v25
	ds_write_b16_d16_hi v2, v3 offset:9040
	v_cvt_pk_bf16_f32 v3, 0, v26
	ds_write_b16_d16_hi v2, v3 offset:9312
	v_cvt_pk_bf16_f32 v3, 0, v27
	ds_write_b16_d16_hi v2, v3 offset:9584
	v_cvt_pk_bf16_f32 v3, 0, v20
	ds_write_b16_d16_hi v2, v3 offset:8800
	v_cvt_pk_bf16_f32 v3, 0, v21
	ds_write_b16_d16_hi v2, v3 offset:9072
	v_cvt_pk_bf16_f32 v3, 0, v22
	ds_write_b16_d16_hi v2, v3 offset:9344
	v_cvt_pk_bf16_f32 v3, 0, v23
	ds_write_b16_d16_hi v2, v3 offset:9616
	v_cvt_pk_bf16_f32 v3, 0, v16
	ds_write_b16_d16_hi v2, v3 offset:13056
	v_cvt_pk_bf16_f32 v3, 0, v17
	ds_write_b16_d16_hi v2, v3 offset:13328
	v_cvt_pk_bf16_f32 v3, 0, v18
	ds_write_b16_d16_hi v2, v3 offset:13600
	v_cvt_pk_bf16_f32 v3, 0, v19
	ds_write_b16_d16_hi v2, v3 offset:13872
	v_cvt_pk_bf16_f32 v3, 0, v12
	ds_write_b16_d16_hi v2, v3 offset:13088
	v_cvt_pk_bf16_f32 v3, 0, v13
	ds_write_b16_d16_hi v2, v3 offset:13360
	v_cvt_pk_bf16_f32 v3, 0, v14
	ds_write_b16_d16_hi v2, v3 offset:13632
	v_cvt_pk_bf16_f32 v3, 0, v15
	ds_write_b16_d16_hi v2, v3 offset:13904
	v_cvt_pk_bf16_f32 v3, 0, v8
	ds_write_b16_d16_hi v2, v3 offset:13120
	v_cvt_pk_bf16_f32 v3, 0, v9
	ds_write_b16_d16_hi v2, v3 offset:13392
	v_cvt_pk_bf16_f32 v3, 0, v10
	ds_write_b16_d16_hi v2, v3 offset:13664
	v_cvt_pk_bf16_f32 v3, 0, v11
	ds_write_b16_d16_hi v2, v3 offset:13936
	v_cvt_pk_bf16_f32 v3, 0, v4
	ds_write_b16_d16_hi v2, v3 offset:13152
	v_cvt_pk_bf16_f32 v3, 0, v5
	ds_write_b16_d16_hi v2, v3 offset:13424
	v_cvt_pk_bf16_f32 v3, 0, v6
	ds_write_b16_d16_hi v2, v3 offset:13696
	v_cvt_pk_bf16_f32 v64, 0, v64
	v_cvt_pk_bf16_f32 v3, 0, v7
	ds_write_b16_d16_hi v2, v64
	ds_write_b16_d16_hi v2, v3 offset:13968
	v_ashrrev_i32_e32 v2, 31, v1
	s_lshl_b64 s[4:5], s[24:25], 1
	v_lshrrev_b32_e32 v2, 28, v2
	s_add_u32 s6, s51, s4
	v_add_u32_e32 v2, v1, v2
	s_addc_u32 s7, s52, s5
	s_lshl_b64 s[4:5], s[36:37], 1
	v_ashrrev_i32_e32 v6, 4, v2
	v_and_b32_e32 v2, -16, v2
	s_add_u32 s4, s6, s4
	v_sub_u32_e32 v2, v1, v2
	v_ashrrev_i32_e32 v7, 31, v6
	s_addc_u32 s5, s7, s5
	v_mul_lo_u32 v3, v6, s65
	v_lshlrev_b32_e32 v8, 3, v2
	v_lshlrev_b64 v[6:7], 11, v[6:7]
	v_ashrrev_i32_e32 v9, 31, v8
	v_lshl_add_u64 v[6:7], s[4:5], 0, v[6:7]
	v_lshl_add_u64 v[10:11], v[8:9], 1, v[6:7]
	v_add_u32_e32 v6, 0x100, v1
	v_ashrrev_i32_e32 v7, 31, v6
	v_lshl_add_u32 v2, v2, 4, v3
	v_lshrrev_b32_e32 v7, 28, v7
	s_waitcnt lgkmcnt(0)
	s_barrier
; template <int WM, int WN>
; __device__ __forceinline__ void store_tile_bf16(const f32x4 (&acc)[WM][WN], u16* dst, int ld, char* smem) {
;     ...
;   constexpr int CPR = BN / 8;
; #pragma unroll
;   for (int i = 0; i < BM * CPR / 256; ++i) {
;     int q = tid + 256 * i, row = q / CPR, c = q % CPR;
;     uint4 v = *reinterpret_cast<const uint4*>(T + row * STR + c * 8);
;     *reinterpret_cast<uint4*>(dst + (size_t)row * ld + c * 8) = v;
;   }
	ds_read_b128 v[2:5], v2
	v_add_u32_e32 v7, v6, v7
	v_ashrrev_i32_e32 v12, 4, v7
	v_and_b32_e32 v7, -16, v7
	v_sub_u32_e32 v13, v6, v7
	v_mul_lo_u32 v6, v12, s65
	v_lshl_add_u32 v6, v13, 4, v6
	ds_read_b128 v[6:9], v6
	s_waitcnt lgkmcnt(1)
	global_store_dwordx4 v[10:11], v[2:5], off
	s_add_i32 s66, s66, s61
	s_cmp_lt_i32 s66, s62
	v_lshlrev_b32_e32 v2, 3, v13
	v_ashrrev_i32_e32 v13, 31, v12
	v_lshlrev_b64 v[4:5], 11, v[12:13]
	v_ashrrev_i32_e32 v3, 31, v2
	v_lshl_add_u64 v[4:5], s[4:5], 0, v[4:5]
	v_lshl_add_u64 v[2:3], v[2:3], 1, v[4:5]
	s_waitcnt lgkmcnt(0)
	global_store_dwordx4 v[2:3], v[6:9], off
	v_add_u32_e32 v2, 0x200, v1
	v_ashrrev_i32_e32 v3, 31, v2
	v_lshrrev_b32_e32 v3, 28, v3
	v_add_u32_e32 v3, v2, v3
	v_ashrrev_i32_e32 v6, 4, v3
	v_and_b32_e32 v3, -16, v3
	v_sub_u32_e32 v2, v2, v3
	v_ashrrev_i32_e32 v7, 31, v6
	v_mul_lo_u32 v3, v6, s65
	v_lshlrev_b32_e32 v8, 3, v2
	v_lshlrev_b64 v[6:7], 11, v[6:7]
	v_ashrrev_i32_e32 v9, 31, v8
	v_lshl_add_u64 v[6:7], s[4:5], 0, v[6:7]
	v_lshl_add_u64 v[10:11], v[8:9], 1, v[6:7]
	v_add_u32_e32 v6, 0x300, v1
	v_ashrrev_i32_e32 v7, 31, v6
	v_lshl_add_u32 v2, v2, 4, v3
	v_lshrrev_b32_e32 v7, 28, v7
	ds_read_b128 v[2:5], v2
	v_add_u32_e32 v7, v6, v7
	v_ashrrev_i32_e32 v12, 4, v7
	v_and_b32_e32 v7, -16, v7
	v_sub_u32_e32 v13, v6, v7
	v_mul_lo_u32 v6, v12, s65
	v_lshl_add_u32 v6, v13, 4, v6
	ds_read_b128 v[6:9], v6
	s_waitcnt lgkmcnt(1)
	global_store_dwordx4 v[10:11], v[2:5], off
	s_nop 1
	v_lshlrev_b32_e32 v2, 3, v13
	v_ashrrev_i32_e32 v13, 31, v12
	v_lshlrev_b64 v[4:5], 11, v[12:13]
	v_ashrrev_i32_e32 v3, 31, v2
	v_lshl_add_u64 v[4:5], s[4:5], 0, v[4:5]
	v_lshl_add_u64 v[2:3], v[2:3], 1, v[4:5]
	s_waitcnt lgkmcnt(0)
	global_store_dwordx4 v[2:3], v[6:9], off
	v_add_u32_e32 v2, 0x400, v1
	v_ashrrev_i32_e32 v3, 31, v2
	v_lshrrev_b32_e32 v3, 28, v3
	v_add_u32_e32 v3, v2, v3
	v_ashrrev_i32_e32 v6, 4, v3
	v_and_b32_e32 v3, -16, v3
	v_sub_u32_e32 v2, v2, v3
	v_ashrrev_i32_e32 v7, 31, v6
	v_mul_lo_u32 v3, v6, s65
	v_lshlrev_b32_e32 v8, 3, v2
	v_lshlrev_b64 v[6:7], 11, v[6:7]
	v_ashrrev_i32_e32 v9, 31, v8
	v_lshl_add_u64 v[6:7], s[4:5], 0, v[6:7]
	v_lshl_add_u64 v[10:11], v[8:9], 1, v[6:7]
	v_add_u32_e32 v6, 0x500, v1
	v_ashrrev_i32_e32 v7, 31, v6
	v_lshl_add_u32 v2, v2, 4, v3
	v_lshrrev_b32_e32 v7, 28, v7
	ds_read_b128 v[2:5], v2
	v_add_u32_e32 v7, v6, v7
	v_ashrrev_i32_e32 v12, 4, v7
	v_and_b32_e32 v7, -16, v7
	v_sub_u32_e32 v13, v6, v7
	v_mul_lo_u32 v6, v12, s65
	v_lshl_add_u32 v6, v13, 4, v6
	ds_read_b128 v[6:9], v6
	s_waitcnt lgkmcnt(1)
	global_store_dwordx4 v[10:11], v[2:5], off
	s_nop 1
	v_lshlrev_b32_e32 v2, 3, v13
	v_ashrrev_i32_e32 v13, 31, v12
	v_lshlrev_b64 v[4:5], 11, v[12:13]
	v_ashrrev_i32_e32 v3, 31, v2
	v_lshl_add_u64 v[4:5], s[4:5], 0, v[4:5]
	v_lshl_add_u64 v[2:3], v[2:3], 1, v[4:5]
	s_waitcnt lgkmcnt(0)
	global_store_dwordx4 v[2:3], v[6:9], off
	v_add_u32_e32 v2, 0x600, v1
	v_ashrrev_i32_e32 v3, 31, v2
	v_lshrrev_b32_e32 v3, 28, v3
	v_add_u32_e32 v3, v2, v3
	v_ashrrev_i32_e32 v6, 4, v3
	v_and_b32_e32 v3, -16, v3
	v_sub_u32_e32 v2, v2, v3
	v_ashrrev_i32_e32 v7, 31, v6
	v_mul_lo_u32 v3, v6, s65
	v_lshlrev_b32_e32 v8, 3, v2
	v_lshlrev_b64 v[6:7], 11, v[6:7]
	v_ashrrev_i32_e32 v9, 31, v8
	v_lshl_add_u64 v[6:7], s[4:5], 0, v[6:7]
	v_add_u32_e32 v1, 0x700, v1
	v_lshl_add_u64 v[10:11], v[8:9], 1, v[6:7]
	v_ashrrev_i32_e32 v6, 31, v1
	v_lshrrev_b32_e32 v6, 28, v6
	v_lshl_add_u32 v2, v2, 4, v3
	v_add_u32_e32 v6, v1, v6
	ds_read_b128 v[2:5], v2
	v_ashrrev_i32_e32 v12, 4, v6
	v_and_b32_e32 v6, -16, v6
	v_sub_u32_e32 v1, v1, v6
	v_mul_lo_u32 v6, v12, s65
	v_lshl_add_u32 v6, v1, 4, v6
	ds_read_b128 v[6:9], v6
	v_ashrrev_i32_e32 v13, 31, v12
	s_waitcnt lgkmcnt(1)
	global_store_dwordx4 v[10:11], v[2:5], off
	s_nop 1
	v_lshlrev_b32_e32 v2, 3, v1
	v_lshlrev_b64 v[4:5], 11, v[12:13]
	v_ashrrev_i32_e32 v3, 31, v2
	v_lshl_add_u64 v[4:5], s[4:5], 0, v[4:5]
	v_lshl_add_u64 v[2:3], v[2:3], 1, v[4:5]
	s_waitcnt lgkmcnt(0)
	global_store_dwordx4 v[2:3], v[6:9], off
	s_cbranch_scc0 .LBB0_278

; __device__ void phase_merge(const Params& p, int layer, char* smem) {
;     ...
;         [&](int s) {
;           int seg = s / 48, r = s - seg * 48;
;           if (r == 31) {
; #pragma unroll
;             for (int n = 0; n < 4; ++n) {
;               float bm = bmp[seg * 1024 + n * 16];
; #pragma unroll
;               for (int m = 0; m < 4; ++m)
; #pragma unroll
;                 for (int j = 0; j < 4; ++j) {
;                   GL[((m * 4 + n) * 4 + j) * 256] = f2bf(1.f / (1.f + __expf(-(acc[m][n][j] + bm))));
;                   acc[m][n][j] = 0.f;
;                 }
;             }
.LBB0_274:
	s_cmp_eq_u32 s8, 31
	s_cbranch_scc0 .LBB0_276
	s_mul_i32 s4, s67, 0xab
	s_lshr_b32 s4, s4, 1
	s_and_b32 s14, s4, 0x7000
	v_lshl_add_u64 v[2:3], v[230:231], 0, s[14:15]
	global_load_dword v164, v[2:3], off
	global_load_dword v165, v[2:3], off offset:64
	global_load_dword v166, v[2:3], off offset:128
	global_load_dword v1, v[2:3], off offset:192
	s_waitcnt vmcnt(3)
	v_add_f32_e32 v2, v160, v164
	v_add_f32_e32 v3, v161, v164
	v_mul_f32_e32 v2, 0xbfb8aa3b, v2
	v_add_f32_e32 v167, v162, v164
	v_mul_f32_e32 v3, 0xbfb8aa3b, v3
	v_exp_f32_e32 v2, v2
	v_add_f32_e32 v168, v163, v164
	v_mul_f32_e32 v167, 0xbfb8aa3b, v167
	v_exp_f32_e32 v3, v3
	v_mul_f32_e32 v168, 0xbfb8aa3b, v168
	v_exp_f32_e32 v167, v167
	v_exp_f32_e32 v168, v168
	v_add_f32_e32 v2, 1.0, v2
	v_add_f32_e32 v3, 1.0, v3
	v_add_f32_e32 v169, v144, v164
	v_add_f32_e32 v167, 1.0, v167
	v_mul_f32_e32 v169, 0xbfb8aa3b, v169
	v_add_f32_e32 v168, 1.0, v168
	v_exp_f32_e32 v169, v169
	s_nop 0
	v_add_f32_e32 v169, 1.0, v169
	v_div_scale_f32 v174, s[4:5], 1.0, v3, 1.0
	v_div_scale_f32 v176, s[6:7], 1.0, v167, 1.0
	v_div_scale_f32 v178, s[8:9], 1.0, v168, 1.0
	v_add_f32_e32 v170, v145, v164
	s_mov_b64 vcc, s[4:5]
	v_mul_f32_e32 v170, 0xbfb8aa3b, v170
	v_rcp_f32_e32 v2, v2
	s_mov_b64 vcc, s[6:7]
	v_exp_f32_e32 v170, v170
	v_rcp_f32_e32 v3, v3
	s_mov_b64 vcc, s[8:9]
	v_div_scale_f32 v180, s[10:11], 1.0, v169, 1.0
	v_cvt_pk_bf16_f32 v2, 0, v2
	v_rcp_f32_e32 v167, v167
	ds_write_b16_d16_hi v234, v2 offset:32768
	v_cvt_pk_bf16_f32 v2, 0, v3
	v_rcp_f32_e32 v168, v168
	ds_write_b16_d16_hi v234, v2 offset:33280
	v_cvt_pk_bf16_f32 v2, 0, v167
	ds_write_b16_d16_hi v234, v2 offset:33792
	v_cvt_pk_bf16_f32 v2, 0, v168
	v_add_f32_e32 v3, 1.0, v170
	s_mov_b64 vcc, s[10:11]
	ds_write_b16_d16_hi v234, v2 offset:34304
	v_rcp_f32_e32 v2, v169
	s_nop 0
	v_cvt_pk_bf16_f32 v2, 0, v2
	ds_write_b16_d16_hi v234, v2 offset:40960
	v_add_f32_e32 v167, v146, v164
	v_mul_f32_e32 v167, 0xbfb8aa3b, v167
	v_exp_f32_e32 v167, v167
	v_rcp_f32_e32 v2, v3
	v_add_f32_e32 v3, 1.0, v167
	v_cvt_pk_bf16_f32 v2, 0, v2
	ds_write_b16_d16_hi v234, v2 offset:41472
	v_add_f32_e32 v167, v147, v164
	v_mul_f32_e32 v167, 0xbfb8aa3b, v167
	v_exp_f32_e32 v167, v167
	v_rcp_f32_e32 v2, v3
	v_add_f32_e32 v3, 1.0, v167
	v_cvt_pk_bf16_f32 v2, 0, v2
	ds_write_b16_d16_hi v234, v2 offset:41984
	v_add_f32_e32 v167, v128, v164
	v_mul_f32_e32 v167, 0xbfb8aa3b, v167
	v_exp_f32_e32 v167, v167
	v_rcp_f32_e32 v2, v3
	v_add_f32_e32 v3, 1.0, v167
	v_cvt_pk_bf16_f32 v2, 0, v2
	ds_write_b16_d16_hi v234, v2 offset:42496
	v_add_f32_e32 v167, v129, v164
	v_mul_f32_e32 v167, 0xbfb8aa3b, v167
	v_exp_f32_e32 v167, v167
	v_rcp_f32_e32 v2, v3
	v_add_f32_e32 v3, 1.0, v167
	v_cvt_pk_bf16_f32 v2, 0, v2
	ds_write_b16_d16_hi v234, v2 offset:49152
	v_add_f32_e32 v167, v130, v164
	v_mul_f32_e32 v167, 0xbfb8aa3b, v167
	v_exp_f32_e32 v167, v167
	v_rcp_f32_e32 v2, v3
	v_add_f32_e32 v3, 1.0, v167
	v_cvt_pk_bf16_f32 v2, 0, v2
	ds_write_b16_d16_hi v234, v2 offset:49664
	v_add_f32_e32 v167, v131, v164
	v_mul_f32_e32 v167, 0xbfb8aa3b, v167
	v_exp_f32_e32 v167, v167
	v_rcp_f32_e32 v2, v3
	v_add_f32_e32 v3, 1.0, v167
	v_cvt_pk_bf16_f32 v2, 0, v2
	ds_write_b16_d16_hi v234, v2 offset:50176
	v_add_f32_e32 v167, v112, v164
	v_mul_f32_e32 v167, 0xbfb8aa3b, v167
	v_exp_f32_e32 v167, v167
	v_rcp_f32_e32 v2, v3
	v_add_f32_e32 v3, 1.0, v167
	v_cvt_pk_bf16_f32 v2, 0, v2
	ds_write_b16_d16_hi v234, v2 offset:50688
	v_add_f32_e32 v167, v113, v164
	v_mul_f32_e32 v167, 0xbfb8aa3b, v167
	v_exp_f32_e32 v167, v167
	v_rcp_f32_e32 v2, v3
	v_add_f32_e32 v3, 1.0, v167
	v_cvt_pk_bf16_f32 v2, 0, v2
	ds_write_b16_d16_hi v234, v2 offset:57344
	v_add_f32_e32 v167, v114, v164
	v_mul_f32_e32 v167, 0xbfb8aa3b, v167
	v_exp_f32_e32 v167, v167
	v_rcp_f32_e32 v2, v3
	v_add_f32_e32 v3, 1.0, v167
	v_cvt_pk_bf16_f32 v2, 0, v2
	ds_write_b16_d16_hi v234, v2 offset:57856
	v_add_f32_e32 v164, v115, v164
	v_mul_f32_e32 v164, 0xbfb8aa3b, v164
	v_exp_f32_e32 v164, v164
	v_rcp_f32_e32 v2, v3
	v_add_f32_e32 v3, 1.0, v164
	v_cvt_pk_bf16_f32 v2, 0, v2
	ds_write_b16_d16_hi v234, v2 offset:58368
	s_waitcnt vmcnt(2)
	v_add_f32_e32 v164, v156, v165
	v_mul_f32_e32 v164, 0xbfb8aa3b, v164
	v_exp_f32_e32 v164, v164
	v_rcp_f32_e32 v2, v3
	v_add_f32_e32 v3, 1.0, v164
	v_cvt_pk_bf16_f32 v2, 0, v2
	ds_write_b16_d16_hi v234, v2 offset:58880
	v_add_f32_e32 v164, v157, v165
	v_mul_f32_e32 v164, 0xbfb8aa3b, v164
	v_exp_f32_e32 v164, v164
	v_rcp_f32_e32 v2, v3
	v_add_f32_e32 v3, 1.0, v164
	v_cvt_pk_bf16_f32 v2, 0, v2
	ds_write_b16_d16_hi v234, v2 offset:34816
	v_add_f32_e32 v164, v158, v165
	v_mul_f32_e32 v164, 0xbfb8aa3b, v164
	v_exp_f32_e32 v164, v164
	v_rcp_f32_e32 v2, v3
	v_add_f32_e32 v3, 1.0, v164
	v_cvt_pk_bf16_f32 v2, 0, v2
	ds_write_b16_d16_hi v234, v2 offset:35328
	v_add_f32_e32 v164, v159, v165
	v_mul_f32_e32 v164, 0xbfb8aa3b, v164
	v_exp_f32_e32 v164, v164
	v_rcp_f32_e32 v2, v3
	v_add_f32_e32 v3, 1.0, v164
	v_cvt_pk_bf16_f32 v2, 0, v2
	ds_write_b16_d16_hi v234, v2 offset:35840
	v_add_f32_e32 v164, v140, v165
	v_mul_f32_e32 v164, 0xbfb8aa3b, v164
	v_exp_f32_e32 v164, v164
	v_rcp_f32_e32 v2, v3
	v_add_f32_e32 v3, 1.0, v164
	v_cvt_pk_bf16_f32 v2, 0, v2
	ds_write_b16_d16_hi v234, v2 offset:36352
	v_add_f32_e32 v164, v141, v165
	v_mul_f32_e32 v164, 0xbfb8aa3b, v164
	v_exp_f32_e32 v164, v164
	v_rcp_f32_e32 v2, v3
	v_add_f32_e32 v3, 1.0, v164
	v_cvt_pk_bf16_f32 v2, 0, v2
	ds_write_b16_d16_hi v234, v2 offset:43008
	v_add_f32_e32 v164, v142, v165
	v_mul_f32_e32 v164, 0xbfb8aa3b, v164
	v_exp_f32_e32 v164, v164
	v_rcp_f32_e32 v2, v3
	v_add_f32_e32 v3, 1.0, v164
	v_cvt_pk_bf16_f32 v2, 0, v2
	ds_write_b16_d16_hi v234, v2 offset:43520
; __device__ void phase_merge(const Params& p, int layer, char* smem) {
;     ...
;         [&](int s) {
;           int seg = s / 48, r = s - seg * 48;
;           if (r == 31) {
; #pragma unroll
;             for (int n = 0; n < 4; ++n) {
;               float bm = bmp[seg * 1024 + n * 16];
; #pragma unroll
;               for (int m = 0; m < 4; ++m)
; #pragma unroll
;                 for (int j = 0; j < 4; ++j) {
;                   GL[((m * 4 + n) * 4 + j) * 256] = f2bf(1.f / (1.f + __expf(-(acc[m][n][j] + bm))));
;                   acc[m][n][j] = 0.f;
;                 }
;             }
	v_add_f32_e32 v164, v143, v165
	v_mul_f32_e32 v164, 0xbfb8aa3b, v164
	v_exp_f32_e32 v164, v164
	v_rcp_f32_e32 v2, v3
	v_add_f32_e32 v3, 1.0, v164
	v_cvt_pk_bf16_f32 v2, 0, v2
	ds_write_b16_d16_hi v234, v2 offset:44032
	v_add_f32_e32 v164, v124, v165
	v_mul_f32_e32 v164, 0xbfb8aa3b, v164
	v_exp_f32_e32 v164, v164
	v_rcp_f32_e32 v2, v3
	v_add_f32_e32 v3, 1.0, v164
	v_cvt_pk_bf16_f32 v2, 0, v2
	ds_write_b16_d16_hi v234, v2 offset:44544
	v_add_f32_e32 v164, v125, v165
	v_mul_f32_e32 v164, 0xbfb8aa3b, v164
	v_exp_f32_e32 v164, v164
	v_rcp_f32_e32 v2, v3
	v_add_f32_e32 v3, 1.0, v164
	v_cvt_pk_bf16_f32 v2, 0, v2
	ds_write_b16_d16_hi v234, v2 offset:51200
	v_add_f32_e32 v164, v126, v165
	v_mul_f32_e32 v164, 0xbfb8aa3b, v164
	v_exp_f32_e32 v164, v164
	v_rcp_f32_e32 v2, v3
	v_add_f32_e32 v3, 1.0, v164
	v_cvt_pk_bf16_f32 v2, 0, v2
	ds_write_b16_d16_hi v234, v2 offset:51712
	v_add_f32_e32 v164, v127, v165
	v_mul_f32_e32 v164, 0xbfb8aa3b, v164
	v_exp_f32_e32 v164, v164
	v_rcp_f32_e32 v2, v3
	v_add_f32_e32 v3, 1.0, v164
	v_cvt_pk_bf16_f32 v2, 0, v2
	ds_write_b16_d16_hi v234, v2 offset:52224
	v_add_f32_e32 v164, v108, v165
	v_mul_f32_e32 v164, 0xbfb8aa3b, v164
	v_exp_f32_e32 v164, v164
	v_rcp_f32_e32 v2, v3
	v_add_f32_e32 v3, 1.0, v164
	v_cvt_pk_bf16_f32 v2, 0, v2
	ds_write_b16_d16_hi v234, v2 offset:52736
	v_add_f32_e32 v164, v109, v165
	v_mul_f32_e32 v164, 0xbfb8aa3b, v164
	v_exp_f32_e32 v164, v164
	v_rcp_f32_e32 v2, v3
	v_add_f32_e32 v3, 1.0, v164
	v_cvt_pk_bf16_f32 v2, 0, v2
	ds_write_b16_d16_hi v234, v2 offset:59392
	v_add_f32_e32 v164, v110, v165
	v_mul_f32_e32 v164, 0xbfb8aa3b, v164
	v_exp_f32_e32 v164, v164
	v_rcp_f32_e32 v2, v3
	v_add_f32_e32 v3, 1.0, v164
	v_cvt_pk_bf16_f32 v2, 0, v2
	ds_write_b16_d16_hi v234, v2 offset:59904
	v_add_f32_e32 v164, v111, v165
	v_mul_f32_e32 v164, 0xbfb8aa3b, v164
	v_exp_f32_e32 v164, v164
	v_rcp_f32_e32 v2, v3
	v_add_f32_e32 v3, 1.0, v164
	v_cvt_pk_bf16_f32 v2, 0, v2
	ds_write_b16_d16_hi v234, v2 offset:60416
	s_waitcnt vmcnt(1)
	v_add_f32_e32 v164, v152, v166
	v_mul_f32_e32 v164, 0xbfb8aa3b, v164
	v_exp_f32_e32 v164, v164
	v_rcp_f32_e32 v2, v3
	v_add_f32_e32 v3, 1.0, v164
	v_cvt_pk_bf16_f32 v2, 0, v2
	ds_write_b16_d16_hi v234, v2 offset:60928
	v_add_f32_e32 v164, v153, v166
	v_mul_f32_e32 v164, 0xbfb8aa3b, v164
	v_exp_f32_e32 v164, v164
	v_rcp_f32_e32 v2, v3
	v_add_f32_e32 v3, 1.0, v164
	v_cvt_pk_bf16_f32 v2, 0, v2
	ds_write_b16_d16_hi v234, v2 offset:36864
	v_add_f32_e32 v164, v154, v166
	v_mul_f32_e32 v164, 0xbfb8aa3b, v164
	v_exp_f32_e32 v164, v164
	v_rcp_f32_e32 v2, v3
	v_add_f32_e32 v3, 1.0, v164
	v_cvt_pk_bf16_f32 v2, 0, v2
	ds_write_b16_d16_hi v234, v2 offset:37376
	v_add_f32_e32 v164, v155, v166
	v_mul_f32_e32 v164, 0xbfb8aa3b, v164
	v_exp_f32_e32 v164, v164
	v_rcp_f32_e32 v2, v3
	v_add_f32_e32 v3, 1.0, v164
	v_cvt_pk_bf16_f32 v2, 0, v2
	ds_write_b16_d16_hi v234, v2 offset:37888
	v_add_f32_e32 v164, v136, v166
	v_mul_f32_e32 v164, 0xbfb8aa3b, v164
	v_exp_f32_e32 v164, v164
	v_rcp_f32_e32 v2, v3
	v_add_f32_e32 v3, 1.0, v164
	v_cvt_pk_bf16_f32 v2, 0, v2
	ds_write_b16_d16_hi v234, v2 offset:38400
	v_add_f32_e32 v164, v137, v166
	v_mul_f32_e32 v164, 0xbfb8aa3b, v164
	v_exp_f32_e32 v164, v164
	v_rcp_f32_e32 v2, v3
	v_add_f32_e32 v3, 1.0, v164
	v_cvt_pk_bf16_f32 v2, 0, v2
	ds_write_b16_d16_hi v234, v2 offset:45056
	v_add_f32_e32 v164, v138, v166
	v_mul_f32_e32 v164, 0xbfb8aa3b, v164
	v_exp_f32_e32 v164, v164
	v_rcp_f32_e32 v2, v3
	v_add_f32_e32 v3, 1.0, v164
	v_cvt_pk_bf16_f32 v2, 0, v2
	ds_write_b16_d16_hi v234, v2 offset:45568
	v_add_f32_e32 v164, v139, v166
	v_mul_f32_e32 v164, 0xbfb8aa3b, v164
	v_exp_f32_e32 v164, v164
	v_rcp_f32_e32 v2, v3
	v_add_f32_e32 v3, 1.0, v164
	v_cvt_pk_bf16_f32 v2, 0, v2
	ds_write_b16_d16_hi v234, v2 offset:46080
	v_add_f32_e32 v164, v120, v166
	v_mul_f32_e32 v164, 0xbfb8aa3b, v164
	v_exp_f32_e32 v164, v164
	v_rcp_f32_e32 v2, v3
	v_add_f32_e32 v3, 1.0, v164
	v_cvt_pk_bf16_f32 v2, 0, v2
	ds_write_b16_d16_hi v234, v2 offset:46592
	v_add_f32_e32 v164, v121, v166
	v_mul_f32_e32 v164, 0xbfb8aa3b, v164
	v_exp_f32_e32 v164, v164
	v_rcp_f32_e32 v2, v3
	v_add_f32_e32 v3, 1.0, v164
	v_cvt_pk_bf16_f32 v2, 0, v2
	ds_write_b16_d16_hi v234, v2 offset:53248
	v_add_f32_e32 v164, v122, v166
	v_mul_f32_e32 v164, 0xbfb8aa3b, v164
	v_exp_f32_e32 v164, v164
	v_rcp_f32_e32 v2, v3
	v_add_f32_e32 v3, 1.0, v164
	v_cvt_pk_bf16_f32 v2, 0, v2
	ds_write_b16_d16_hi v234, v2 offset:53760
	v_add_f32_e32 v164, v123, v166
	v_mul_f32_e32 v164, 0xbfb8aa3b, v164
	v_exp_f32_e32 v164, v164
	v_rcp_f32_e32 v2, v3
	v_add_f32_e32 v3, 1.0, v164
	v_cvt_pk_bf16_f32 v2, 0, v2
	ds_write_b16_d16_hi v234, v2 offset:54272
	v_add_f32_e32 v164, v100, v166
	v_mul_f32_e32 v164, 0xbfb8aa3b, v164
	v_exp_f32_e32 v164, v164
	v_rcp_f32_e32 v2, v3
	v_add_f32_e32 v3, 1.0, v164
	v_cvt_pk_bf16_f32 v2, 0, v2
	ds_write_b16_d16_hi v234, v2 offset:54784
	v_add_f32_e32 v164, v101, v166
	v_mul_f32_e32 v164, 0xbfb8aa3b, v164
	v_exp_f32_e32 v164, v164
	v_rcp_f32_e32 v2, v3
	v_add_f32_e32 v3, 1.0, v164
	v_cvt_pk_bf16_f32 v2, 0, v2
	ds_write_b16_d16_hi v234, v2 offset:61440
	v_add_f32_e32 v164, v102, v166
	v_mul_f32_e32 v164, 0xbfb8aa3b, v164
	v_exp_f32_e32 v164, v164
	v_rcp_f32_e32 v2, v3
	v_add_f32_e32 v3, 1.0, v164
	v_cvt_pk_bf16_f32 v2, 0, v2
	ds_write_b16_d16_hi v234, v2 offset:61952
	v_add_f32_e32 v164, v103, v166
	v_mul_f32_e32 v164, 0xbfb8aa3b, v164
	v_exp_f32_e32 v164, v164
	v_rcp_f32_e32 v2, v3
	v_add_f32_e32 v3, 1.0, v164
	v_cvt_pk_bf16_f32 v2, 0, v2
	ds_write_b16_d16_hi v234, v2 offset:62464
	s_waitcnt vmcnt(0)
; __device__ void phase_merge(const Params& p, int layer, char* smem) {
;     ...
;         [&](int s) {
;           int seg = s / 48, r = s - seg * 48;
;           if (r == 31) {
; #pragma unroll
;             for (int n = 0; n < 4; ++n) {
;               float bm = bmp[seg * 1024 + n * 16];
; #pragma unroll
;               for (int m = 0; m < 4; ++m)
; #pragma unroll
;                 for (int j = 0; j < 4; ++j) {
;                   GL[((m * 4 + n) * 4 + j) * 256] = f2bf(1.f / (1.f + __expf(-(acc[m][n][j] + bm))));
;                   acc[m][n][j] = 0.f;
;                 }
;             }
	v_add_f32_e32 v164, v148, v1
	v_mul_f32_e32 v164, 0xbfb8aa3b, v164
	v_exp_f32_e32 v164, v164
	v_rcp_f32_e32 v2, v3
	v_add_f32_e32 v3, 1.0, v164
	v_cvt_pk_bf16_f32 v2, 0, v2
	ds_write_b16_d16_hi v234, v2 offset:62976
	v_add_f32_e32 v164, v149, v1
	v_mul_f32_e32 v164, 0xbfb8aa3b, v164
	v_exp_f32_e32 v164, v164
	v_rcp_f32_e32 v2, v3
	v_add_f32_e32 v3, 1.0, v164
	v_cvt_pk_bf16_f32 v2, 0, v2
	ds_write_b16_d16_hi v234, v2 offset:38912
	v_add_f32_e32 v164, v150, v1
	v_mul_f32_e32 v164, 0xbfb8aa3b, v164
	v_exp_f32_e32 v164, v164
	v_rcp_f32_e32 v2, v3
	v_add_f32_e32 v3, 1.0, v164
	v_cvt_pk_bf16_f32 v2, 0, v2
	ds_write_b16_d16_hi v234, v2 offset:39424
	v_add_f32_e32 v164, v151, v1
	v_mul_f32_e32 v164, 0xbfb8aa3b, v164
	v_exp_f32_e32 v164, v164
	v_rcp_f32_e32 v2, v3
	v_add_f32_e32 v3, 1.0, v164
	v_cvt_pk_bf16_f32 v2, 0, v2
	ds_write_b16_d16_hi v234, v2 offset:39936
	v_add_f32_e32 v164, v132, v1
	v_mul_f32_e32 v164, 0xbfb8aa3b, v164
	v_exp_f32_e32 v164, v164
	v_rcp_f32_e32 v2, v3
	v_add_f32_e32 v3, 1.0, v164
	v_cvt_pk_bf16_f32 v2, 0, v2
	ds_write_b16_d16_hi v234, v2 offset:40448
	v_add_f32_e32 v164, v133, v1
	v_mul_f32_e32 v164, 0xbfb8aa3b, v164
	v_exp_f32_e32 v164, v164
	v_rcp_f32_e32 v2, v3
	v_add_f32_e32 v3, 1.0, v164
	v_cvt_pk_bf16_f32 v2, 0, v2
	ds_write_b16_d16_hi v234, v2 offset:47104
	v_add_f32_e32 v164, v134, v1
	v_mul_f32_e32 v164, 0xbfb8aa3b, v164
	v_exp_f32_e32 v164, v164
	v_rcp_f32_e32 v2, v3
	v_add_f32_e32 v3, 1.0, v164
	v_cvt_pk_bf16_f32 v2, 0, v2
	ds_write_b16_d16_hi v234, v2 offset:47616
	v_add_f32_e32 v164, v135, v1
	v_mul_f32_e32 v164, 0xbfb8aa3b, v164
	v_exp_f32_e32 v164, v164
	v_rcp_f32_e32 v2, v3
	v_add_f32_e32 v3, 1.0, v164
	v_cvt_pk_bf16_f32 v2, 0, v2
	ds_write_b16_d16_hi v234, v2 offset:48128
	v_add_f32_e32 v164, v116, v1
	v_mul_f32_e32 v164, 0xbfb8aa3b, v164
	v_exp_f32_e32 v164, v164
	v_rcp_f32_e32 v2, v3
	v_add_f32_e32 v3, 1.0, v164
	v_cvt_pk_bf16_f32 v2, 0, v2
	ds_write_b16_d16_hi v234, v2 offset:48640
	v_add_f32_e32 v164, v117, v1
	v_mul_f32_e32 v164, 0xbfb8aa3b, v164
	v_exp_f32_e32 v164, v164
	v_rcp_f32_e32 v2, v3
	v_add_f32_e32 v3, 1.0, v164
	v_cvt_pk_bf16_f32 v2, 0, v2
	ds_write_b16_d16_hi v234, v2 offset:55296
	v_add_f32_e32 v164, v118, v1
	v_mul_f32_e32 v164, 0xbfb8aa3b, v164
	v_exp_f32_e32 v164, v164
	v_rcp_f32_e32 v2, v3
	v_add_f32_e32 v3, 1.0, v164
	v_cvt_pk_bf16_f32 v2, 0, v2
	ds_write_b16_d16_hi v234, v2 offset:55808
	v_add_f32_e32 v164, v119, v1
	v_mul_f32_e32 v164, 0xbfb8aa3b, v164
	v_exp_f32_e32 v164, v164
	v_rcp_f32_e32 v2, v3
	v_add_f32_e32 v3, 1.0, v164
	v_cvt_pk_bf16_f32 v2, 0, v2
	ds_write_b16_d16_hi v234, v2 offset:56320
	v_add_f32_e32 v164, v104, v1
	v_mul_f32_e32 v164, 0xbfb8aa3b, v164
	v_exp_f32_e32 v164, v164
	v_rcp_f32_e32 v2, v3
	v_add_f32_e32 v3, 1.0, v164
	v_cvt_pk_bf16_f32 v2, 0, v2
	ds_write_b16_d16_hi v234, v2 offset:56832
	v_add_f32_e32 v164, v105, v1
	v_mul_f32_e32 v164, 0xbfb8aa3b, v164
	v_exp_f32_e32 v164, v164
	v_rcp_f32_e32 v2, v3
	v_add_f32_e32 v3, 1.0, v164
	v_cvt_pk_bf16_f32 v2, 0, v2
	ds_write_b16_d16_hi v234, v2 offset:63488
	v_add_f32_e32 v164, v106, v1
	v_mul_f32_e32 v164, 0xbfb8aa3b, v164
	v_exp_f32_e32 v164, v164
	v_rcp_f32_e32 v2, v3
	v_add_f32_e32 v3, 1.0, v164
	v_cvt_pk_bf16_f32 v2, 0, v2
	ds_write_b16_d16_hi v234, v2 offset:64000
	v_add_f32_e32 v1, v107, v1
	v_mul_f32_e32 v1, 0xbfb8aa3b, v1
	v_exp_f32_e32 v1, v1
	v_rcp_f32_e32 v2, v3
	s_nop 0
	v_cvt_pk_bf16_f32 v2, 0, v2
	v_add_f32_e32 v3, 1.0, v1
	ds_write_b16_d16_hi v234, v2 offset:64512
	v_mov_b32_e32 v1, v0
	v_mov_b32_e32 v2, v0
	v_rcp_f32_e32 v3, v3
	s_nop 0
	v_cvt_pk_bf16_f32 v3, 0, v3
	ds_write_b16_d16_hi v234, v3 offset:65024
	s_mov_b64 s[4:5], -1

; template <int WM, int WN> ...
;   static_assert(WM == 4 && WN == 4, "128x128 block tile");
;   constexpr int APAN = 128 * 64 + PPAD, BPAN = 128 * 64 + PPAD;
;   bf16x8 fa0[4], fb0[4], fa1[4], fb1[4];
; #pragma unroll
;   for (int n = 0; n < 4; ++n) fb0[n] = LDSF(cur + boff + n * 1024);
; #pragma unroll
;   for (int m = 0; m < 4; ++m) fa0[m] = LDSF(cur + aoff + m * 1024);
;   acc[3][0] = MFMA16(pa, pb0, acc[3][0]);
;   acc[3][1] = MFMA16(pa, pb1, acc[3][1]);
;   acc[3][2] = MFMA16(pa, pb2, acc[3][2]);
;   acc[3][3] = MFMA16(pa, pb3, acc[3][3]);
; #pragma unroll
;   for (int n = 0; n < 4; ++n) acc[0][n] = MFMA16(fa0[0], fb0[n], acc[0][n]);
; #pragma unroll
;   for (int m = 0; m < 4; ++m) fa1[m] = LDSF(cur + aoff + APAN + m * 1024);
; #pragma unroll
;   for (int n = 0; n < 4; ++n) acc[1][n] = MFMA16(fa0[1], fb0[n], acc[1][n]);
; #pragma unroll
;   for (int n = 0; n < 4; ++n) fb1[n] = LDSF(cur + boff + BPAN + n * 1024);
; #pragma unroll
;   for (int n = 0; n < 4; ++n) acc[2][n] = MFMA16(fa0[2], fb0[n], acc[2][n]);
;   *reinterpret_cast<uint4*>(nxt + wao) = a0;
;   *reinterpret_cast<uint4*>(nxt + wao + 32 * 64) = a1;
; #pragma unroll
;   for (int n = 0; n < 4; ++n) acc[3][n] = MFMA16(fa0[3], fb0[n], acc[3][n]);
;   *reinterpret_cast<uint4*>(nxt + wao + 64 * 64) = a2;
;   *reinterpret_cast<uint4*>(nxt + wao + 96 * 64) = a3;
; #pragma unroll
;   for (int n = 0; n < 4; ++n) acc[0][n] = MFMA16(fa1[0], fb1[n], acc[0][n]);
;   *reinterpret_cast<uint4*>(nxt + wbo) = b0;
;   *reinterpret_cast<uint4*>(nxt + wbo + 32 * 64) = b1;
; #pragma unroll
;   for (int n = 0; n < 4; ++n) acc[1][n] = MFMA16(fa1[1], fb1[n], acc[1][n]);
;   *reinterpret_cast<uint4*>(nxt + wbo + 64 * 64) = b2;
;   *reinterpret_cast<uint4*>(nxt + wbo + 96 * 64) = b3;
; #pragma unroll
;   for (int n = 0; n < 4; ++n) acc[2][n] = MFMA16(fa1[2], fb1[n], acc[2][n]);
;   pa = fa1[3];
;   pb0 = fb1[0]; pb1 = fb1[1]; pb2 = fb1[2]; pb3 = fb1[3];
;   SGB_(0x100, 5);
;   SGB_(0x008, 4);
; #pragma unroll
;   for (int i_ = 0; i_ < 11; ++i_) { SGB_(0x008, 1); SGB_(0x100, 1); }
; #pragma unroll
;   for (int i_ = 0; i_ < 8; ++i_) { SGB_(0x008, 2); SGB_(0x200, 1); SGB_(0x020, 1); }
;   SGB_(0x008, 1);
; template <int WM, int WN, typename SrcF, typename PostF>
; __device__ __forceinline__ void gemm_stream(const int nsteps, SrcF src, PostF post, f32x4 (&acc)[WM][WN], char* smem) {
;     ...
; #pragma unroll 1
.LBB0_318:
	s_add_i32 s44, s7, 2
	s_add_i32 s7, s7, 4
	s_min_u32 s7, s7, 15
	s_lshl_b32 s7, s7, 7
	s_add_u32 s92, s10, s7
	s_addc_u32 s93, s11, 0
	s_add_u32 s94, s12, s7
	s_addc_u32 s95, s13, 0
	ds_read_b128 v[144:147], v124
	ds_read_b128 v[128:131], v125 offset:16512
	ds_read_b128 v[132:135], v125 offset:17536
	ds_read_b128 v[136:139], v125 offset:18560
	ds_read_b128 v[140:143], v125 offset:19584
	v_mfma_f32_16x16x32_bf16 v[64:67], v[48:51], v[64:67], v[92:95]
	v_mfma_f32_16x16x32_bf16 v[88:91], v[48:51], v[104:107], v[88:91]
	s_waitcnt vmcnt(7)
	ds_write_b128 v126, v[32:35] offset:33024
	global_load_dwordx4 v[32:35], v116, s[92:93]
	s_add_u32 s48, s10, s7
	s_addc_u32 s49, s11, 0
	v_mfma_f32_16x16x32_bf16 v[80:83], v[48:51], v[112:115], v[80:83]
	v_mfma_f32_16x16x32_bf16 v[48:51], v[48:51], v[108:111], v[56:59]
	s_waitcnt lgkmcnt(4)
	v_mfma_f32_16x16x32_bf16 v[56:59], v[144:147], v[128:131], v[100:103]
	ds_read_b128 v[92:95], v124 offset:1024
	s_waitcnt lgkmcnt(4)
	v_mfma_f32_16x16x32_bf16 v[96:99], v[144:147], v[132:135], v[96:99]
	s_waitcnt vmcnt(7)
	ds_write_b128 v126, v[20:23] offset:35072
	global_load_dwordx4 v[20:23], v118, s[92:93]
	ds_read_b128 v[100:103], v124 offset:2048
	s_waitcnt lgkmcnt(5)
	v_mfma_f32_16x16x32_bf16 v[84:87], v[144:147], v[136:139], v[84:87]
	ds_read_b128 v[104:107], v124 offset:3072
	s_waitcnt lgkmcnt(5)
	v_mfma_f32_16x16x32_bf16 v[76:79], v[144:147], v[140:143], v[76:79]
	ds_read_b128 v[108:111], v124 offset:8256
	s_waitcnt lgkmcnt(4)
	v_mfma_f32_16x16x32_bf16 v[72:75], v[92:95], v[128:131], v[72:75]
	ds_read_b128 v[112:115], v124 offset:9280
	v_mfma_f32_16x16x32_bf16 v[68:71], v[92:95], v[132:135], v[68:71]
	ds_read_b128 v[144:147], v124 offset:10304
	v_mfma_f32_16x16x32_bf16 v[60:63], v[92:95], v[136:139], v[60:63]
	s_waitcnt vmcnt(7)
	ds_write_b128 v126, v[16:19] offset:37120
	global_load_dwordx4 v[16:19], v120, s[92:93]
	ds_read_b128 v[148:151], v124 offset:11328
	v_mfma_f32_16x16x32_bf16 v[52:55], v[92:95], v[140:143], v[52:55]
	ds_read_b128 v[92:95], v125 offset:24768
	s_waitcnt lgkmcnt(7)
	v_mfma_f32_16x16x32_bf16 v[44:47], v[100:103], v[128:131], v[44:47]
	ds_read_b128 v[152:155], v125 offset:25792
	v_mfma_f32_16x16x32_bf16 v[40:43], v[100:103], v[132:135], v[40:43]
	ds_read_b128 v[156:159], v125 offset:26816
	v_mfma_f32_16x16x32_bf16 v[36:39], v[100:103], v[136:139], v[36:39]
	s_waitcnt vmcnt(7)
	ds_write_b128 v126, v[24:27] offset:39168
	global_load_dwordx4 v[24:27], v122, s[92:93]
	ds_read_b128 v[160:163], v125 offset:27840
	v_mfma_f32_16x16x32_bf16 v[28:31], v[100:103], v[140:143], v[28:31]
	s_waitcnt lgkmcnt(10)
	v_mfma_f32_16x16x32_bf16 v[64:67], v[104:107], v[128:131], v[64:67]
	v_mfma_f32_16x16x32_bf16 v[88:91], v[104:107], v[132:135], v[88:91]
	v_mfma_f32_16x16x32_bf16 v[80:83], v[104:107], v[136:139], v[80:83]
	v_mfma_f32_16x16x32_bf16 v[48:51], v[104:107], v[140:143], v[48:51]
	s_waitcnt vmcnt(7)
	ds_write_b128 v126, v[12:15] offset:49536
	global_load_dwordx4 v[12:15], v116, s[94:95]
	s_waitcnt lgkmcnt(5)
	v_mfma_f32_16x16x32_bf16 v[56:59], v[108:111], v[92:95], v[56:59]
	s_add_u32 s48, s12, s7
	s_addc_u32 s49, s13, 0
	s_waitcnt lgkmcnt(4)
	v_mfma_f32_16x16x32_bf16 v[96:99], v[108:111], v[152:155], v[96:99]
	s_min_u32 s7, s44, 12
	s_lshl_b32 s7, s7, 7
	s_waitcnt lgkmcnt(3)
	v_mfma_f32_16x16x32_bf16 v[84:87], v[108:111], v[156:159], v[84:87]
	s_waitcnt lgkmcnt(1)
	v_mfma_f32_16x16x32_bf16 v[76:79], v[108:111], v[160:163], v[76:79]
	s_waitcnt vmcnt(7)
	ds_write_b128 v126, v[8:11] offset:51584
	global_load_dwordx4 v[8:11], v118, s[94:95]
	v_mfma_f32_16x16x32_bf16 v[72:75], v[112:115], v[92:95], v[72:75]
	v_mfma_f32_16x16x32_bf16 v[68:71], v[112:115], v[152:155], v[68:71]
	v_mfma_f32_16x16x32_bf16 v[60:63], v[112:115], v[156:159], v[60:63]
	v_mfma_f32_16x16x32_bf16 v[52:55], v[112:115], v[160:163], v[52:55]
	v_mfma_f32_16x16x32_bf16 v[44:47], v[144:147], v[92:95], v[44:47]
	s_waitcnt vmcnt(7)
	ds_write_b128 v126, v[4:7] offset:53632
	global_load_dwordx4 v[4:7], v120, s[94:95]
	v_mfma_f32_16x16x32_bf16 v[40:43], v[144:147], v[152:155], v[40:43]
	s_add_u32 s48, s10, s7
	s_addc_u32 s49, s11, 0
	s_add_u32 s50, s12, s7
	v_mfma_f32_16x16x32_bf16 v[36:39], v[144:147], v[156:159], v[36:39]
	s_addc_u32 s51, s13, 0
	v_mfma_f32_16x16x32_bf16 v[28:31], v[144:147], v[160:163], v[28:31]
	v_mfma_f32_16x16x32_bf16 v[92:95], v[148:151], v[92:95], v[64:67]
	s_waitcnt vmcnt(7)
	ds_write_b128 v126, v[0:3] offset:55680
	global_load_dwordx4 v[0:3], v122, s[94:95]
	v_mfma_f32_16x16x32_bf16 v[88:91], v[148:151], v[152:155], v[88:91]
	v_mfma_f32_16x16x32_bf16 v[80:83], v[148:151], v[156:159], v[80:83]
	v_mfma_f32_16x16x32_bf16 v[100:103], v[148:151], v[160:163], v[48:51]
	s_waitcnt lgkmcnt(0)
	s_barrier
; template <int WM, int WN> ...
;   static_assert(WM == 4 && WN == 4, "128x128 block tile");
;   constexpr int APAN = 128 * 64 + PPAD, BPAN = 128 * 64 + PPAD;
;   bf16x8 fa0[4], fb0[4], fa1[4], fb1[4];
; #pragma unroll
;   for (int n = 0; n < 4; ++n) fb0[n] = LDSF(cur + boff + n * 1024);
; #pragma unroll
;   for (int m = 0; m < 4; ++m) fa0[m] = LDSF(cur + aoff + m * 1024);
;   acc[3][0] = MFMA16(pa, pb0, acc[3][0]);
;   acc[3][1] = MFMA16(pa, pb1, acc[3][1]);
;   acc[3][2] = MFMA16(pa, pb2, acc[3][2]);
;   acc[3][3] = MFMA16(pa, pb3, acc[3][3]);
; #pragma unroll
;   for (int n = 0; n < 4; ++n) acc[0][n] = MFMA16(fa0[0], fb0[n], acc[0][n]);
; #pragma unroll
;   for (int m = 0; m < 4; ++m) fa1[m] = LDSF(cur + aoff + APAN + m * 1024);
; #pragma unroll
;   for (int n = 0; n < 4; ++n) acc[1][n] = MFMA16(fa0[1], fb0[n], acc[1][n]);
; #pragma unroll
;   for (int n = 0; n < 4; ++n) fb1[n] = LDSF(cur + boff + BPAN + n * 1024);
; #pragma unroll
;   for (int n = 0; n < 4; ++n) acc[2][n] = MFMA16(fa0[2], fb0[n], acc[2][n]);
;   *reinterpret_cast<uint4*>(nxt + wao) = a0;
;   *reinterpret_cast<uint4*>(nxt + wao + 32 * 64) = a1;
; #pragma unroll
;   for (int n = 0; n < 4; ++n) acc[3][n] = MFMA16(fa0[3], fb0[n], acc[3][n]);
;   *reinterpret_cast<uint4*>(nxt + wao + 64 * 64) = a2;
;   *reinterpret_cast<uint4*>(nxt + wao + 96 * 64) = a3;
; #pragma unroll
;   for (int n = 0; n < 4; ++n) acc[0][n] = MFMA16(fa1[0], fb1[n], acc[0][n]);
;   *reinterpret_cast<uint4*>(nxt + wbo) = b0;
;   *reinterpret_cast<uint4*>(nxt + wbo + 32 * 64) = b1;
; #pragma unroll
;   for (int n = 0; n < 4; ++n) acc[1][n] = MFMA16(fa1[1], fb1[n], acc[1][n]);
;   *reinterpret_cast<uint4*>(nxt + wbo + 64 * 64) = b2;
;   *reinterpret_cast<uint4*>(nxt + wbo + 96 * 64) = b3;
; #pragma unroll
;   for (int n = 0; n < 4; ++n) acc[2][n] = MFMA16(fa1[2], fb1[n], acc[2][n]);
;   pa = fa1[3];
;   pb0 = fb1[0]; pb1 = fb1[1]; pb2 = fb1[2]; pb3 = fb1[3];
;   SGB_(0x100, 5);
;   SGB_(0x008, 4);
; #pragma unroll
;   for (int i_ = 0; i_ < 11; ++i_) { SGB_(0x008, 1); SGB_(0x100, 1); }
; #pragma unroll
;   for (int i_ = 0; i_ < 8; ++i_) { SGB_(0x008, 2); SGB_(0x200, 1); SGB_(0x020, 1); }
;   SGB_(0x008, 1);
; template <int WM, int WN, typename SrcF, typename PostF>
; __device__ __forceinline__ void gemm_stream(const int nsteps, SrcF src, PostF post, f32x4 (&acc)[WM][WN], char* smem) {
;     ...
; #pragma unroll 1
	s_nop 0
	ds_read_b128 v[48:51], v124 offset:33024
	ds_read_b128 v[108:111], v125 offset:49536
	ds_read_b128 v[128:131], v125 offset:50560
	ds_read_b128 v[132:135], v125 offset:51584
	ds_read_b128 v[136:139], v125 offset:52608
	s_waitcnt lgkmcnt(3)
	v_mfma_f32_16x16x32_bf16 v[140:143], v[48:51], v[108:111], v[56:59]
	s_waitcnt lgkmcnt(2)
	v_mfma_f32_16x16x32_bf16 v[96:99], v[48:51], v[128:131], v[96:99]
	s_waitcnt vmcnt(7)
	ds_write_b128 v126, v[32:35]
	global_load_dwordx4 v[32:35], v116, s[48:49] offset:384
	s_waitcnt lgkmcnt(2)
	v_mfma_f32_16x16x32_bf16 v[84:87], v[48:51], v[132:135], v[84:87]
	s_waitcnt lgkmcnt(0)
	v_mfma_f32_16x16x32_bf16 v[76:79], v[48:51], v[136:139], v[76:79]
	ds_read_b128 v[48:51], v124 offset:34048
	s_waitcnt lgkmcnt(0)
	v_mfma_f32_16x16x32_bf16 v[72:75], v[48:51], v[108:111], v[72:75]
	s_waitcnt vmcnt(7)
	ds_write_b128 v126, v[20:23] offset:2048
	global_load_dwordx4 v[20:23], v118, s[48:49] offset:384
	ds_read_b128 v[56:59], v124 offset:35072
	v_mfma_f32_16x16x32_bf16 v[68:71], v[48:51], v[128:131], v[68:71]
	ds_read_b128 v[144:147], v124 offset:36096
	v_mfma_f32_16x16x32_bf16 v[60:63], v[48:51], v[132:135], v[60:63]
	ds_read_b128 v[148:151], v124 offset:41280
	v_mfma_f32_16x16x32_bf16 v[52:55], v[48:51], v[136:139], v[52:55]
	ds_read_b128 v[152:155], v124 offset:42304
	s_waitcnt lgkmcnt(3)
	v_mfma_f32_16x16x32_bf16 v[44:47], v[56:59], v[108:111], v[44:47]
	s_waitcnt vmcnt(7)
	ds_write_b128 v126, v[16:19] offset:4096
	global_load_dwordx4 v[16:19], v120, s[48:49] offset:384
	ds_read_b128 v[156:159], v124 offset:43328
	v_mfma_f32_16x16x32_bf16 v[40:43], v[56:59], v[128:131], v[40:43]
	ds_read_b128 v[48:51], v124 offset:44352
	v_mfma_f32_16x16x32_bf16 v[36:39], v[56:59], v[132:135], v[36:39]
	ds_read_b128 v[64:67], v125 offset:57792
	v_mfma_f32_16x16x32_bf16 v[28:31], v[56:59], v[136:139], v[28:31]
	s_waitcnt vmcnt(7)
	ds_write_b128 v126, v[24:27] offset:6144
	global_load_dwordx4 v[24:27], v122, s[48:49] offset:384
	ds_read_b128 v[104:107], v125 offset:58816
	s_waitcnt lgkmcnt(8)
	v_mfma_f32_16x16x32_bf16 v[92:95], v[144:147], v[108:111], v[92:95]
	ds_read_b128 v[112:115], v125 offset:59840
	v_mfma_f32_16x16x32_bf16 v[88:91], v[144:147], v[128:131], v[88:91]
	ds_read_b128 v[108:111], v125 offset:60864
	v_mfma_f32_16x16x32_bf16 v[80:83], v[144:147], v[132:135], v[80:83]
	v_mfma_f32_16x16x32_bf16 v[56:59], v[144:147], v[136:139], v[100:103]
	s_waitcnt vmcnt(7)
	ds_write_b128 v126, v[12:15] offset:16512
	global_load_dwordx4 v[12:15], v116, s[50:51] offset:384
	s_waitcnt lgkmcnt(5)
	v_mfma_f32_16x16x32_bf16 v[100:103], v[148:151], v[64:67], v[140:143]
	s_waitcnt lgkmcnt(3)
	v_mfma_f32_16x16x32_bf16 v[96:99], v[148:151], v[104:107], v[96:99]
	s_waitcnt lgkmcnt(2)
	v_mfma_f32_16x16x32_bf16 v[84:87], v[148:151], v[112:115], v[84:87]
	s_waitcnt vmcnt(7)
	ds_write_b128 v126, v[8:11] offset:18560
	global_load_dwordx4 v[8:11], v118, s[50:51] offset:384
	s_waitcnt lgkmcnt(2)
	v_mfma_f32_16x16x32_bf16 v[76:79], v[148:151], v[108:111], v[76:79]
	v_mfma_f32_16x16x32_bf16 v[72:75], v[152:155], v[64:67], v[72:75]
	v_mfma_f32_16x16x32_bf16 v[68:71], v[152:155], v[104:107], v[68:71]
	v_mfma_f32_16x16x32_bf16 v[60:63], v[152:155], v[112:115], v[60:63]
	s_waitcnt vmcnt(7)
	ds_write_b128 v126, v[4:7] offset:20608
	global_load_dwordx4 v[4:7], v120, s[50:51] offset:384
	v_mfma_f32_16x16x32_bf16 v[52:55], v[152:155], v[108:111], v[52:55]
	v_mfma_f32_16x16x32_bf16 v[44:47], v[156:159], v[64:67], v[44:47]
	v_mfma_f32_16x16x32_bf16 v[40:43], v[156:159], v[104:107], v[40:43]
	s_waitcnt vmcnt(7)
	ds_write_b128 v126, v[0:3] offset:22656
	global_load_dwordx4 v[0:3], v122, s[50:51] offset:384
	v_mfma_f32_16x16x32_bf16 v[36:39], v[156:159], v[112:115], v[36:39]
	v_mfma_f32_16x16x32_bf16 v[28:31], v[156:159], v[108:111], v[28:31]
	s_cmp_lt_u32 s44, 12
	s_mov_b32 s7, s44
	s_waitcnt lgkmcnt(0)
	s_barrier
	s_cbranch_scc1 .LBB0_318
	ds_read_b128 v[144:147], v124
	ds_read_b128 v[128:131], v125 offset:16512
	ds_read_b128 v[132:135], v125 offset:17536
	ds_read_b128 v[136:139], v125 offset:18560
	ds_read_b128 v[140:143], v125 offset:19584
	v_mfma_f32_16x16x32_bf16 v[64:67], v[48:51], v[64:67], v[92:95]
	s_add_i32 s44, s7, 2
	s_add_i32 s7, s7, 4
	s_min_u32 s7, s7, 15
	v_mfma_f32_16x16x32_bf16 v[88:91], v[48:51], v[104:107], v[88:91]
	s_lshl_b32 s7, s7, 7
	s_add_u32 s48, s10, s7
	s_addc_u32 s49, s11, 0
	v_mfma_f32_16x16x32_bf16 v[80:83], v[48:51], v[112:115], v[80:83]
	v_mfma_f32_16x16x32_bf16 v[48:51], v[48:51], v[108:111], v[56:59]
	s_waitcnt lgkmcnt(3)
	v_mfma_f32_16x16x32_bf16 v[56:59], v[144:147], v[128:131], v[100:103]
	ds_read_b128 v[92:95], v124 offset:1024
	s_waitcnt lgkmcnt(3)
	v_mfma_f32_16x16x32_bf16 v[96:99], v[144:147], v[132:135], v[96:99]
	ds_read_b128 v[100:103], v124 offset:2048
	s_waitcnt lgkmcnt(3)
	v_mfma_f32_16x16x32_bf16 v[84:87], v[144:147], v[136:139], v[84:87]
	ds_read_b128 v[104:107], v124 offset:3072
	s_waitcnt lgkmcnt(3)
	v_mfma_f32_16x16x32_bf16 v[76:79], v[144:147], v[140:143], v[76:79]
	ds_read_b128 v[108:111], v124 offset:8256
	s_waitcnt lgkmcnt(3)
	v_mfma_f32_16x16x32_bf16 v[72:75], v[92:95], v[128:131], v[72:75]
	ds_read_b128 v[112:115], v124 offset:9280
	v_mfma_f32_16x16x32_bf16 v[68:71], v[92:95], v[132:135], v[68:71]
	ds_read_b128 v[144:147], v124 offset:10304
	v_mfma_f32_16x16x32_bf16 v[60:63], v[92:95], v[136:139], v[60:63]
	ds_read_b128 v[148:151], v124 offset:11328
	v_mfma_f32_16x16x32_bf16 v[52:55], v[92:95], v[140:143], v[52:55]
	ds_read_b128 v[92:95], v125 offset:24768
	s_waitcnt lgkmcnt(6)
; template <int WM, int WN> ...
;   static_assert(WM == 4 && WN == 4, "128x128 block tile");
;   constexpr int APAN = 128 * 64 + PPAD, BPAN = 128 * 64 + PPAD;
;   bf16x8 fa0[4], fb0[4], fa1[4], fb1[4];
; #pragma unroll
;   for (int n = 0; n < 4; ++n) fb0[n] = LDSF(cur + boff + n * 1024);
; #pragma unroll
;   for (int m = 0; m < 4; ++m) fa0[m] = LDSF(cur + aoff + m * 1024);
;   acc[3][0] = MFMA16(pa, pb0, acc[3][0]);
;   acc[3][1] = MFMA16(pa, pb1, acc[3][1]);
;   acc[3][2] = MFMA16(pa, pb2, acc[3][2]);
;   acc[3][3] = MFMA16(pa, pb3, acc[3][3]);
; #pragma unroll
;   for (int n = 0; n < 4; ++n) acc[0][n] = MFMA16(fa0[0], fb0[n], acc[0][n]);
; #pragma unroll
;   for (int m = 0; m < 4; ++m) fa1[m] = LDSF(cur + aoff + APAN + m * 1024);
; #pragma unroll
;   for (int n = 0; n < 4; ++n) acc[1][n] = MFMA16(fa0[1], fb0[n], acc[1][n]);
; #pragma unroll
;   for (int n = 0; n < 4; ++n) fb1[n] = LDSF(cur + boff + BPAN + n * 1024);
; #pragma unroll
;   for (int n = 0; n < 4; ++n) acc[2][n] = MFMA16(fa0[2], fb0[n], acc[2][n]);
;   *reinterpret_cast<uint4*>(nxt + wao) = a0;
;   *reinterpret_cast<uint4*>(nxt + wao + 32 * 64) = a1;
; #pragma unroll
;   for (int n = 0; n < 4; ++n) acc[3][n] = MFMA16(fa0[3], fb0[n], acc[3][n]);
;   *reinterpret_cast<uint4*>(nxt + wao + 64 * 64) = a2;
;   *reinterpret_cast<uint4*>(nxt + wao + 96 * 64) = a3;
; #pragma unroll
;   for (int n = 0; n < 4; ++n) acc[0][n] = MFMA16(fa1[0], fb1[n], acc[0][n]);
;   *reinterpret_cast<uint4*>(nxt + wbo) = b0;
;   *reinterpret_cast<uint4*>(nxt + wbo + 32 * 64) = b1;
; #pragma unroll
;   for (int n = 0; n < 4; ++n) acc[1][n] = MFMA16(fa1[1], fb1[n], acc[1][n]);
;   *reinterpret_cast<uint4*>(nxt + wbo + 64 * 64) = b2;
;   *reinterpret_cast<uint4*>(nxt + wbo + 96 * 64) = b3;
; #pragma unroll
;   for (int n = 0; n < 4; ++n) acc[2][n] = MFMA16(fa1[2], fb1[n], acc[2][n]);
;   pa = fa1[3];
;   pb0 = fb1[0]; pb1 = fb1[1]; pb2 = fb1[2]; pb3 = fb1[3];
;   SGB_(0x100, 5);
;   SGB_(0x008, 4);
; #pragma unroll
;   for (int i_ = 0; i_ < 11; ++i_) { SGB_(0x008, 1); SGB_(0x100, 1); }
; #pragma unroll
;   for (int i_ = 0; i_ < 8; ++i_) { SGB_(0x008, 2); SGB_(0x200, 1); SGB_(0x020, 1); }
;   SGB_(0x008, 1);
; template <int WM, int WN, typename SrcF, typename PostF>
; __device__ __forceinline__ void gemm_stream(const int nsteps, SrcF src, PostF post, f32x4 (&acc)[WM][WN], char* smem) {
;     ...
; #pragma unroll 1
	v_mfma_f32_16x16x32_bf16 v[44:47], v[100:103], v[128:131], v[44:47]
	ds_read_b128 v[152:155], v125 offset:25792
	v_mfma_f32_16x16x32_bf16 v[40:43], v[100:103], v[132:135], v[40:43]
	ds_read_b128 v[156:159], v125 offset:26816
	v_mfma_f32_16x16x32_bf16 v[36:39], v[100:103], v[136:139], v[36:39]
	ds_read_b128 v[160:163], v125 offset:27840
	v_mfma_f32_16x16x32_bf16 v[28:31], v[100:103], v[140:143], v[28:31]
	s_waitcnt lgkmcnt(8)
	v_mfma_f32_16x16x32_bf16 v[64:67], v[104:107], v[128:131], v[64:67]
	s_waitcnt vmcnt(7)
	ds_write_b128 v126, v[32:35] offset:33024
	v_mfma_f32_16x16x32_bf16 v[88:91], v[104:107], v[132:135], v[88:91]
	v_mfma_f32_16x16x32_bf16 v[80:83], v[104:107], v[136:139], v[80:83]
	s_waitcnt vmcnt(6)
	ds_write_b128 v126, v[20:23] offset:35072
	v_mfma_f32_16x16x32_bf16 v[48:51], v[104:107], v[140:143], v[48:51]
	s_waitcnt lgkmcnt(5)
	v_mfma_f32_16x16x32_bf16 v[56:59], v[108:111], v[92:95], v[56:59]
	s_waitcnt vmcnt(5)
	ds_write_b128 v126, v[16:19] offset:37120
	s_add_u32 s48, s12, s7
	s_addc_u32 s49, s13, 0
	s_waitcnt lgkmcnt(5)
	v_mfma_f32_16x16x32_bf16 v[96:99], v[108:111], v[152:155], v[96:99]
	s_min_u32 s7, s44, 12
	s_lshl_b32 s7, s7, 7
	s_waitcnt lgkmcnt(4)
	v_mfma_f32_16x16x32_bf16 v[84:87], v[108:111], v[156:159], v[84:87]
	s_waitcnt vmcnt(4)
	ds_write_b128 v126, v[24:27] offset:39168
	s_waitcnt lgkmcnt(4)
	v_mfma_f32_16x16x32_bf16 v[76:79], v[108:111], v[160:163], v[76:79]
	v_mfma_f32_16x16x32_bf16 v[72:75], v[112:115], v[92:95], v[72:75]
	s_waitcnt vmcnt(3)
	ds_write_b128 v126, v[12:15] offset:49536
	v_mfma_f32_16x16x32_bf16 v[68:71], v[112:115], v[152:155], v[68:71]
	v_mfma_f32_16x16x32_bf16 v[60:63], v[112:115], v[156:159], v[60:63]
	s_waitcnt vmcnt(2)
	ds_write_b128 v126, v[8:11] offset:51584
	v_mfma_f32_16x16x32_bf16 v[52:55], v[112:115], v[160:163], v[52:55]
	v_mfma_f32_16x16x32_bf16 v[44:47], v[144:147], v[92:95], v[44:47]
	s_waitcnt vmcnt(1)
	ds_write_b128 v126, v[4:7] offset:53632
	v_mfma_f32_16x16x32_bf16 v[40:43], v[144:147], v[152:155], v[40:43]
	s_add_u32 s48, s10, s7
	s_addc_u32 s49, s11, 0
	s_add_u32 s50, s12, s7
	v_mfma_f32_16x16x32_bf16 v[36:39], v[144:147], v[156:159], v[36:39]
	s_waitcnt vmcnt(0)
	ds_write_b128 v126, v[0:3] offset:55680
	s_addc_u32 s51, s13, 0
	v_mfma_f32_16x16x32_bf16 v[28:31], v[144:147], v[160:163], v[28:31]
	v_mfma_f32_16x16x32_bf16 v[92:95], v[148:151], v[92:95], v[64:67]
	v_mfma_f32_16x16x32_bf16 v[88:91], v[148:151], v[152:155], v[88:91]
	v_mfma_f32_16x16x32_bf16 v[80:83], v[148:151], v[156:159], v[80:83]
	v_mfma_f32_16x16x32_bf16 v[100:103], v[148:151], v[160:163], v[48:51]
	s_waitcnt lgkmcnt(0)
	s_barrier
	s_nop 0
	ds_read_b128 v[48:51], v124 offset:33024
	ds_read_b128 v[108:111], v125 offset:49536
	ds_read_b128 v[128:131], v125 offset:50560
	ds_read_b128 v[132:135], v125 offset:51584
	ds_read_b128 v[136:139], v125 offset:52608
	s_waitcnt lgkmcnt(3)
	v_mfma_f32_16x16x32_bf16 v[140:143], v[48:51], v[108:111], v[56:59]
	s_waitcnt lgkmcnt(2)
	v_mfma_f32_16x16x32_bf16 v[96:99], v[48:51], v[128:131], v[96:99]
	s_waitcnt lgkmcnt(1)
	v_mfma_f32_16x16x32_bf16 v[84:87], v[48:51], v[132:135], v[84:87]
	s_waitcnt lgkmcnt(0)
	v_mfma_f32_16x16x32_bf16 v[76:79], v[48:51], v[136:139], v[76:79]
	ds_read_b128 v[48:51], v124 offset:34048
	s_waitcnt lgkmcnt(0)
	v_mfma_f32_16x16x32_bf16 v[72:75], v[48:51], v[108:111], v[72:75]
	ds_read_b128 v[56:59], v124 offset:35072
	v_mfma_f32_16x16x32_bf16 v[68:71], v[48:51], v[128:131], v[68:71]
	ds_read_b128 v[144:147], v124 offset:36096
	v_mfma_f32_16x16x32_bf16 v[60:63], v[48:51], v[132:135], v[60:63]
	ds_read_b128 v[148:151], v124 offset:41280
	v_mfma_f32_16x16x32_bf16 v[52:55], v[48:51], v[136:139], v[52:55]
	ds_read_b128 v[152:155], v124 offset:42304
	s_waitcnt lgkmcnt(3)
	v_mfma_f32_16x16x32_bf16 v[44:47], v[56:59], v[108:111], v[44:47]
	ds_read_b128 v[156:159], v124 offset:43328
	v_mfma_f32_16x16x32_bf16 v[40:43], v[56:59], v[128:131], v[40:43]
	ds_read_b128 v[48:51], v124 offset:44352
	v_mfma_f32_16x16x32_bf16 v[36:39], v[56:59], v[132:135], v[36:39]
	ds_read_b128 v[64:67], v125 offset:57792
	v_mfma_f32_16x16x32_bf16 v[28:31], v[56:59], v[136:139], v[28:31]
	ds_read_b128 v[104:107], v125 offset:58816
	s_waitcnt lgkmcnt(6)
	v_mfma_f32_16x16x32_bf16 v[92:95], v[144:147], v[108:111], v[92:95]
	ds_read_b128 v[112:115], v125 offset:59840
	v_mfma_f32_16x16x32_bf16 v[88:91], v[144:147], v[128:131], v[88:91]
	ds_read_b128 v[108:111], v125 offset:60864
	v_mfma_f32_16x16x32_bf16 v[80:83], v[144:147], v[132:135], v[80:83]
	v_mfma_f32_16x16x32_bf16 v[56:59], v[144:147], v[136:139], v[100:103]
	ds_write_b128 v126, v[32:35]
	s_waitcnt lgkmcnt(4)
	v_mfma_f32_16x16x32_bf16 v[100:103], v[148:151], v[64:67], v[140:143]
	s_waitcnt lgkmcnt(3)
	v_mfma_f32_16x16x32_bf16 v[96:99], v[148:151], v[104:107], v[96:99]
	ds_write_b128 v126, v[20:23] offset:2048
	s_waitcnt lgkmcnt(3)
	v_mfma_f32_16x16x32_bf16 v[84:87], v[148:151], v[112:115], v[84:87]
	s_waitcnt lgkmcnt(2)
	v_mfma_f32_16x16x32_bf16 v[76:79], v[148:151], v[108:111], v[76:79]
	ds_write_b128 v126, v[16:19] offset:4096
	v_mfma_f32_16x16x32_bf16 v[72:75], v[152:155], v[64:67], v[72:75]
	v_mfma_f32_16x16x32_bf16 v[68:71], v[152:155], v[104:107], v[68:71]
	ds_write_b128 v126, v[24:27] offset:6144
	v_mfma_f32_16x16x32_bf16 v[60:63], v[152:155], v[112:115], v[60:63]
	v_mfma_f32_16x16x32_bf16 v[52:55], v[152:155], v[108:111], v[52:55]
	ds_write_b128 v126, v[12:15] offset:16512
	v_mfma_f32_16x16x32_bf16 v[44:47], v[156:159], v[64:67], v[44:47]
	v_mfma_f32_16x16x32_bf16 v[40:43], v[156:159], v[104:107], v[40:43]
	ds_write_b128 v126, v[8:11] offset:18560
	v_mfma_f32_16x16x32_bf16 v[36:39], v[156:159], v[112:115], v[36:39]
	v_mfma_f32_16x16x32_bf16 v[28:31], v[156:159], v[108:111], v[28:31]
	ds_write_b128 v126, v[4:7] offset:20608
	ds_write_b128 v126, v[0:3] offset:22656
	s_cmp_lt_u32 s44, 14
	s_mov_b32 s7, s44
	s_waitcnt lgkmcnt(0)
	s_barrier
; #define MFMA16(a, b, c) __builtin_amdgcn_mfma_f32_16x16x32_bf16(a, b, c, 0, 0, 0)
; template <int WM, int WN, typename SrcF, typename PostF>
; __device__ __forceinline__ void gemm_stream(const int nsteps, SrcF src, PostF post, f32x4 (&acc)[WM][WN], char* smem) {
;     ...
;   acc[3][0] = MFMA16(pa, pb0, acc[3][0]);
;   acc[3][1] = MFMA16(pa, pb1, acc[3][1]);
;   acc[3][2] = MFMA16(pa, pb2, acc[3][2]);
;   acc[3][3] = MFMA16(pa, pb3, acc[3][3]);
; template <int WM, int WN>
; __device__ __forceinline__ void store_tile_bf16(const f32x4 (&acc)[WM][WN], u16* dst, int ld, char* smem) {
;   constexpr int BM = 32 * WM, BN = 32 * WN, STR = BN + 8;
;   const int tid = opaque_tid(), lane = tid & 63, wid = tid >> 6;
;   const int wr = wid >> 1, wc = wid & 1, fr = lane & 15, fq = lane >> 4;
;   u16* T = reinterpret_cast<u16*>(smem);
; #pragma unroll
;   for (int m = 0; m < WM; ++m)
; #pragma unroll
;     for (int n = 0; n < WN; ++n)
; #pragma unroll
;       for (int j = 0; j < 4; ++j)
;         T[(wr * 16 * WM + m * 16 + fq * 4 + j) * STR + wc * 16 * WN + n * 16 + fr] = f2bf(acc[m][n][j]);
;   __syncthreads();
	s_waitcnt vmcnt(5)
	v_mov_b32_e32 v16, v232
	s_waitcnt vmcnt(0)
	v_mfma_f32_16x16x32_bf16 v[0:3], v[48:51], v[64:67], v[92:95]
	v_lshrrev_b32_e32 v18, 2, v16
	v_lshrrev_b32_e32 v17, 1, v16
	v_and_b32_e32 v18, 12, v18
	v_and_or_b32 v17, v17, s40, v18
	v_and_b32_e32 v18, 0x4f, v16
	v_mul_lo_u32 v17, v17, s42
	v_lshl_add_u32 v17, v18, 1, v17
	v_cvt_pk_bf16_f32 v18, 0, v101
	ds_write_b16_d16_hi v17, v18 offset:272
	v_cvt_pk_bf16_f32 v18, 0, v102
	ds_write_b16_d16_hi v17, v18 offset:544
	v_cvt_pk_bf16_f32 v18, 0, v103
	ds_write_b16_d16_hi v17, v18 offset:816
	v_cvt_pk_bf16_f32 v18, 0, v96
	ds_write_b16_d16_hi v17, v18 offset:32
	v_cvt_pk_bf16_f32 v18, 0, v97
	ds_write_b16_d16_hi v17, v18 offset:304
	v_cvt_pk_bf16_f32 v18, 0, v98
	ds_write_b16_d16_hi v17, v18 offset:576
	v_cvt_pk_bf16_f32 v18, 0, v99
	ds_write_b16_d16_hi v17, v18 offset:848
	v_cvt_pk_bf16_f32 v18, 0, v84
	ds_write_b16_d16_hi v17, v18 offset:64
	v_cvt_pk_bf16_f32 v18, 0, v85
	ds_write_b16_d16_hi v17, v18 offset:336
	v_cvt_pk_bf16_f32 v18, 0, v86
	ds_write_b16_d16_hi v17, v18 offset:608
	v_cvt_pk_bf16_f32 v18, 0, v87
	ds_write_b16_d16_hi v17, v18 offset:880
	v_cvt_pk_bf16_f32 v18, 0, v76
	ds_write_b16_d16_hi v17, v18 offset:96
	v_cvt_pk_bf16_f32 v18, 0, v77
	ds_write_b16_d16_hi v17, v18 offset:368
	v_cvt_pk_bf16_f32 v18, 0, v78
	ds_write_b16_d16_hi v17, v18 offset:640
	v_cvt_pk_bf16_f32 v18, 0, v79
	ds_write_b16_d16_hi v17, v18 offset:912
	v_cvt_pk_bf16_f32 v18, 0, v72
	ds_write_b16_d16_hi v17, v18 offset:4352
	v_cvt_pk_bf16_f32 v18, 0, v73
	ds_write_b16_d16_hi v17, v18 offset:4624
	v_cvt_pk_bf16_f32 v18, 0, v74
	ds_write_b16_d16_hi v17, v18 offset:4896
	v_cvt_pk_bf16_f32 v18, 0, v75
	ds_write_b16_d16_hi v17, v18 offset:5168
	v_cvt_pk_bf16_f32 v18, 0, v68
	ds_write_b16_d16_hi v17, v18 offset:4384
	v_cvt_pk_bf16_f32 v18, 0, v69
	ds_write_b16_d16_hi v17, v18 offset:4656
	v_cvt_pk_bf16_f32 v18, 0, v70
	ds_write_b16_d16_hi v17, v18 offset:4928
	v_cvt_pk_bf16_f32 v18, 0, v71
	ds_write_b16_d16_hi v17, v18 offset:5200
	v_cvt_pk_bf16_f32 v18, 0, v60
	ds_write_b16_d16_hi v17, v18 offset:4416
	v_cvt_pk_bf16_f32 v18, 0, v61
	ds_write_b16_d16_hi v17, v18 offset:4688
	v_cvt_pk_bf16_f32 v18, 0, v62
	ds_write_b16_d16_hi v17, v18 offset:4960
	v_cvt_pk_bf16_f32 v18, 0, v63
	ds_write_b16_d16_hi v17, v18 offset:5232
	v_cvt_pk_bf16_f32 v18, 0, v52
	ds_write_b16_d16_hi v17, v18 offset:4448
	v_cvt_pk_bf16_f32 v18, 0, v53
	ds_write_b16_d16_hi v17, v18 offset:4720
	v_cvt_pk_bf16_f32 v18, 0, v54
	ds_write_b16_d16_hi v17, v18 offset:4992
	v_cvt_pk_bf16_f32 v18, 0, v55
	ds_write_b16_d16_hi v17, v18 offset:5264
	v_cvt_pk_bf16_f32 v18, 0, v44
	ds_write_b16_d16_hi v17, v18 offset:8704
	v_cvt_pk_bf16_f32 v18, 0, v45
	ds_write_b16_d16_hi v17, v18 offset:8976
	v_cvt_pk_bf16_f32 v18, 0, v46
	ds_write_b16_d16_hi v17, v18 offset:9248
	v_cvt_pk_bf16_f32 v18, 0, v47
	ds_write_b16_d16_hi v17, v18 offset:9520
	v_cvt_pk_bf16_f32 v18, 0, v40
	ds_write_b16_d16_hi v17, v18 offset:8736
	v_cvt_pk_bf16_f32 v18, 0, v41
	ds_write_b16_d16_hi v17, v18 offset:9008
	v_cvt_pk_bf16_f32 v18, 0, v42
	ds_write_b16_d16_hi v17, v18 offset:9280
	v_cvt_pk_bf16_f32 v18, 0, v43
	ds_write_b16_d16_hi v17, v18 offset:9552
	v_cvt_pk_bf16_f32 v18, 0, v36
	ds_write_b16_d16_hi v17, v18 offset:8768
	v_cvt_pk_bf16_f32 v18, 0, v37
	ds_write_b16_d16_hi v17, v18 offset:9040
	v_cvt_pk_bf16_f32 v18, 0, v38
	ds_write_b16_d16_hi v17, v18 offset:9312
	v_cvt_pk_bf16_f32 v18, 0, v39
	ds_write_b16_d16_hi v17, v18 offset:9584
	v_cvt_pk_bf16_f32 v18, 0, v28
	ds_write_b16_d16_hi v17, v18 offset:8800
	v_cvt_pk_bf16_f32 v18, 0, v29
	ds_write_b16_d16_hi v17, v18 offset:9072
	v_cvt_pk_bf16_f32 v18, 0, v30
	ds_write_b16_d16_hi v17, v18 offset:9344
	v_cvt_pk_bf16_f32 v18, 0, v31
	ds_write_b16_d16_hi v17, v18 offset:9616
	v_cvt_pk_bf16_f32 v0, 0, v0
	ds_write_b16_d16_hi v17, v0 offset:13056
	v_cvt_pk_bf16_f32 v0, 0, v1
	v_mfma_f32_16x16x32_bf16 v[4:7], v[48:51], v[104:107], v[88:91]
	ds_write_b16_d16_hi v17, v0 offset:13328
	v_cvt_pk_bf16_f32 v0, 0, v2
	ds_write_b16_d16_hi v17, v0 offset:13600
	v_cvt_pk_bf16_f32 v0, 0, v3
	ds_write_b16_d16_hi v17, v0 offset:13872
	s_nop 0
	s_nop 1
	v_cvt_pk_bf16_f32 v0, 0, v4
	ds_write_b16_d16_hi v17, v0 offset:13088
	v_cvt_pk_bf16_f32 v0, 0, v5
	v_mfma_f32_16x16x32_bf16 v[8:11], v[48:51], v[112:115], v[80:83]
	ds_write_b16_d16_hi v17, v0 offset:13360
	v_cvt_pk_bf16_f32 v0, 0, v6
	ds_write_b16_d16_hi v17, v0 offset:13632
	v_cvt_pk_bf16_f32 v0, 0, v7
	ds_write_b16_d16_hi v17, v0 offset:13904
	s_nop 0
	s_nop 1
	v_cvt_pk_bf16_f32 v0, 0, v8
	ds_write_b16_d16_hi v17, v0 offset:13120
	v_cvt_pk_bf16_f32 v0, 0, v9
	v_mfma_f32_16x16x32_bf16 v[12:15], v[48:51], v[108:111], v[56:59]
	ds_write_b16_d16_hi v17, v0 offset:13392
	v_cvt_pk_bf16_f32 v0, 0, v10
	ds_write_b16_d16_hi v17, v0 offset:13664
	v_cvt_pk_bf16_f32 v0, 0, v11
	ds_write_b16_d16_hi v17, v0 offset:13936
	s_nop 0
	s_nop 1
	v_cvt_pk_bf16_f32 v0, 0, v12
	ds_write_b16_d16_hi v17, v0 offset:13152
	v_cvt_pk_bf16_f32 v0, 0, v13
	ds_write_b16_d16_hi v17, v0 offset:13424
	v_cvt_pk_bf16_f32 v0, 0, v14
	ds_write_b16_d16_hi v17, v0 offset:13696
	s_lshl_b64 s[8:9], s[8:9], 1
	v_cvt_pk_bf16_f32 v0, 0, v15
	s_add_u32 s8, s26, s8
	ds_write_b16_d16_hi v17, v0 offset:13968
	v_ashrrev_i32_e32 v0, 31, v16
	s_addc_u32 s9, s27, s9
	s_lshl_b32 s6, s6, 7
	v_lshrrev_b32_e32 v0, 28, v0
	s_ashr_i32 s7, s6, 31
	v_add_u32_e32 v0, v16, v0
	s_lshl_b64 s[6:7], s[6:7], 1
	v_ashrrev_i32_e32 v4, 4, v0
	v_and_b32_e32 v0, -16, v0
	s_add_u32 s6, s8, s6
	v_sub_u32_e32 v0, v16, v0
	v_ashrrev_i32_e32 v5, 31, v4
	s_addc_u32 s7, s9, s7
	v_mul_lo_u32 v1, v4, s42
	v_lshlrev_b32_e32 v6, 3, v0
	v_lshlrev_b64 v[4:5], 11, v[4:5]
	v_ashrrev_i32_e32 v7, 31, v6
	v_lshl_add_u64 v[4:5], s[6:7], 0, v[4:5]
	v_lshl_add_u64 v[8:9], v[6:7], 1, v[4:5]
	v_add_u32_e32 v4, 0x100, v16
	v_ashrrev_i32_e32 v5, 31, v4
	v_cvt_pk_bf16_f32 v19, 0, v100
	v_lshl_add_u32 v0, v0, 4, v1
	v_lshrrev_b32_e32 v5, 28, v5
	ds_write_b16_d16_hi v17, v19
	s_waitcnt lgkmcnt(0)
	s_barrier
; template <int WM, int WN>
; __device__ __forceinline__ void store_tile_bf16(const f32x4 (&acc)[WM][WN], u16* dst, int ld, char* smem) {
;     ...
;   constexpr int CPR = BN / 8;
; #pragma unroll
;   for (int i = 0; i < BM * CPR / 256; ++i) {
;     int q = tid + 256 * i, row = q / CPR, c = q % CPR;
;     uint4 v = *reinterpret_cast<const uint4*>(T + row * STR + c * 8);
;     *reinterpret_cast<uint4*>(dst + (size_t)row * ld + c * 8) = v;
;   }
	ds_read_b128 v[0:3], v0
	v_add_u32_e32 v5, v4, v5
	v_ashrrev_i32_e32 v10, 4, v5
	v_and_b32_e32 v5, -16, v5
	v_sub_u32_e32 v11, v4, v5
	v_mul_lo_u32 v4, v10, s42
	v_lshl_add_u32 v4, v11, 4, v4
	ds_read_b128 v[4:7], v4
	s_waitcnt lgkmcnt(1)
	global_store_dwordx4 v[8:9], v[0:3], off
	s_add_i32 s43, s43, s61
	s_cmp_lt_i32 s43, s62
	v_lshlrev_b32_e32 v0, 3, v11
	v_ashrrev_i32_e32 v11, 31, v10
	v_lshlrev_b64 v[2:3], 11, v[10:11]
	v_ashrrev_i32_e32 v1, 31, v0
	v_lshl_add_u64 v[2:3], s[6:7], 0, v[2:3]
	v_lshl_add_u64 v[0:1], v[0:1], 1, v[2:3]
	s_waitcnt lgkmcnt(0)
	global_store_dwordx4 v[0:1], v[4:7], off
	v_add_u32_e32 v0, 0x200, v16
	v_ashrrev_i32_e32 v1, 31, v0
	v_lshrrev_b32_e32 v1, 28, v1
	v_add_u32_e32 v1, v0, v1
	v_ashrrev_i32_e32 v4, 4, v1
	v_and_b32_e32 v1, -16, v1
	v_sub_u32_e32 v0, v0, v1
	v_ashrrev_i32_e32 v5, 31, v4
	v_mul_lo_u32 v1, v4, s42
	v_lshlrev_b32_e32 v6, 3, v0
	v_lshlrev_b64 v[4:5], 11, v[4:5]
	v_ashrrev_i32_e32 v7, 31, v6
	v_lshl_add_u64 v[4:5], s[6:7], 0, v[4:5]
	v_lshl_add_u64 v[8:9], v[6:7], 1, v[4:5]
	v_add_u32_e32 v4, 0x300, v16
	v_ashrrev_i32_e32 v5, 31, v4
	v_lshl_add_u32 v0, v0, 4, v1
	v_lshrrev_b32_e32 v5, 28, v5
	ds_read_b128 v[0:3], v0
	v_add_u32_e32 v5, v4, v5
	v_ashrrev_i32_e32 v10, 4, v5
	v_and_b32_e32 v5, -16, v5
	v_sub_u32_e32 v11, v4, v5
	v_mul_lo_u32 v4, v10, s42
	v_lshl_add_u32 v4, v11, 4, v4
	ds_read_b128 v[4:7], v4
	s_waitcnt lgkmcnt(1)
	global_store_dwordx4 v[8:9], v[0:3], off
	s_nop 1
	v_lshlrev_b32_e32 v0, 3, v11
	v_ashrrev_i32_e32 v11, 31, v10
	v_lshlrev_b64 v[2:3], 11, v[10:11]
	v_ashrrev_i32_e32 v1, 31, v0
	v_lshl_add_u64 v[2:3], s[6:7], 0, v[2:3]
	v_lshl_add_u64 v[0:1], v[0:1], 1, v[2:3]
	s_waitcnt lgkmcnt(0)
	global_store_dwordx4 v[0:1], v[4:7], off
	v_add_u32_e32 v0, 0x400, v16
	v_ashrrev_i32_e32 v1, 31, v0
	v_lshrrev_b32_e32 v1, 28, v1
	v_add_u32_e32 v1, v0, v1
	v_ashrrev_i32_e32 v4, 4, v1
	v_and_b32_e32 v1, -16, v1
	v_sub_u32_e32 v0, v0, v1
	v_ashrrev_i32_e32 v5, 31, v4
	v_mul_lo_u32 v1, v4, s42
	v_lshlrev_b32_e32 v6, 3, v0
	v_lshlrev_b64 v[4:5], 11, v[4:5]
	v_ashrrev_i32_e32 v7, 31, v6
	v_lshl_add_u64 v[4:5], s[6:7], 0, v[4:5]
	v_lshl_add_u64 v[8:9], v[6:7], 1, v[4:5]
	v_add_u32_e32 v4, 0x500, v16
	v_ashrrev_i32_e32 v5, 31, v4
	v_lshl_add_u32 v0, v0, 4, v1
	v_lshrrev_b32_e32 v5, 28, v5
	ds_read_b128 v[0:3], v0
	v_add_u32_e32 v5, v4, v5
	v_ashrrev_i32_e32 v10, 4, v5
	v_and_b32_e32 v5, -16, v5
	v_sub_u32_e32 v11, v4, v5
	v_mul_lo_u32 v4, v10, s42
	v_lshl_add_u32 v4, v11, 4, v4
	ds_read_b128 v[4:7], v4
	s_waitcnt lgkmcnt(1)
	global_store_dwordx4 v[8:9], v[0:3], off
	s_nop 1
	v_lshlrev_b32_e32 v0, 3, v11
	v_ashrrev_i32_e32 v11, 31, v10
	v_lshlrev_b64 v[2:3], 11, v[10:11]
	v_ashrrev_i32_e32 v1, 31, v0
	v_lshl_add_u64 v[2:3], s[6:7], 0, v[2:3]
	v_lshl_add_u64 v[0:1], v[0:1], 1, v[2:3]
	s_waitcnt lgkmcnt(0)
	global_store_dwordx4 v[0:1], v[4:7], off
	v_add_u32_e32 v0, 0x600, v16
	v_ashrrev_i32_e32 v1, 31, v0
	v_lshrrev_b32_e32 v1, 28, v1
	v_add_u32_e32 v1, v0, v1
	v_ashrrev_i32_e32 v4, 4, v1
	v_and_b32_e32 v1, -16, v1
	v_sub_u32_e32 v0, v0, v1
	v_ashrrev_i32_e32 v5, 31, v4
	v_mul_lo_u32 v1, v4, s42
	v_lshlrev_b32_e32 v6, 3, v0
	v_lshlrev_b64 v[4:5], 11, v[4:5]
	v_ashrrev_i32_e32 v7, 31, v6
	v_lshl_add_u64 v[4:5], s[6:7], 0, v[4:5]
	v_lshl_add_u64 v[8:9], v[6:7], 1, v[4:5]
	v_add_u32_e32 v4, 0x700, v16
	v_ashrrev_i32_e32 v5, 31, v4
	v_lshl_add_u32 v0, v0, 4, v1
	v_lshrrev_b32_e32 v5, 28, v5
	ds_read_b128 v[0:3], v0
	v_add_u32_e32 v5, v4, v5
	v_ashrrev_i32_e32 v10, 4, v5
	v_and_b32_e32 v5, -16, v5
	v_sub_u32_e32 v11, v4, v5
	v_mul_lo_u32 v4, v10, s42
	v_lshl_add_u32 v4, v11, 4, v4
	ds_read_b128 v[4:7], v4
	s_waitcnt lgkmcnt(1)
	global_store_dwordx4 v[8:9], v[0:3], off
	s_nop 1
	v_lshlrev_b32_e32 v0, 3, v11
	v_ashrrev_i32_e32 v11, 31, v10
	v_lshlrev_b64 v[2:3], 11, v[10:11]
	v_ashrrev_i32_e32 v1, 31, v0
	v_lshl_add_u64 v[2:3], s[6:7], 0, v[2:3]
	v_lshl_add_u64 v[0:1], v[0:1], 1, v[2:3]
	s_waitcnt lgkmcnt(0)
	global_store_dwordx4 v[0:1], v[4:7], off
	s_cbranch_scc1 .LBB0_317

; __device__ __forceinline__ float bflo(unsigned w) { return __uint_as_float(w << 16); }
; __device__ __forceinline__ float bfhi(unsigned w) { return __uint_as_float(w & 0xffff0000u); }
; __device__ void norm_phase(const Params& p, int layer) {
;     ...
;       const float* xr = (layer == 0) ? p.x : p.out;
;       float4 ov[8];
;       float ss = 0.f;
; #pragma unroll
;       for (int i = 0; i < 8; ++i) {
;         {
;           uint2 ob = *reinterpret_cast<const uint2*>(OUTB + rbase + i * 128);
;           ov[i] = make_float4(bflo(ob.x), bfhi(ob.x), bflo(ob.y), bfhi(ob.y));
;         }
;         xv[i] = *reinterpret_cast<const float4*>(xr + rbase + i * 128);
;       }
; #pragma unroll
;       for (int i = 0; i < 8; ++i) ss += ov[i].x * ov[i].x + ov[i].y * ov[i].y + ov[i].z * ov[i].z + ov[i].w * ov[i].w;
;       ss = half_wave_sum(ss);
;       float rstd = rsqrtf(ss * (1.f / 1024.f) + 1e-6f);
; #pragma unroll
;       for (int i = 0; i < 8; ++i) {
;         float4 g = *reinterpret_cast<const float4*>(p.g_post + (size_t)layer * DM + l32 * 4 + i * 128);
;         xv[i].x += ov[i].x * rstd * g.x;
;         xv[i].y += ov[i].y * rstd * g.y;
;         xv[i].z += ov[i].z * rstd * g.z;
;         xv[i].w += ov[i].w * rstd * g.w;
;         *reinterpret_cast<float4*>(p.out + rbase + i * 128) = xv[i];
;       }
;     }
;     const int nl = layer + 1;
;     if (nl < 4) {
;       float ss = 0.f;
; #pragma unroll
;       for (int i = 0; i < 8; ++i) ss += xv[i].x * xv[i].x + xv[i].y * xv[i].y + xv[i].z * xv[i].z + xv[i].w * xv[i].w;
;       ss = half_wave_sum(ss);
;       float rstd = rsqrtf(ss * (1.f / 1024.f) + 1e-6f);
.LBB0_359:
	v_ashrrev_i32_e32 v39, 31, v38
	v_lshlrev_b64 v[4:5], 10, v[38:39]
	v_or_b32_e32 v4, v4, v32
	v_lshlrev_b64 v[40:41], 1, v[4:5]
	v_lshl_add_u64 v[6:7], s[10:11], 0, v[40:41]
	global_load_dwordx2 v[12:13], v[6:7], off
	global_load_dwordx2 v[14:15], v[6:7], off offset:256
	global_load_dwordx2 v[16:17], v[6:7], off offset:512
	global_load_dwordx2 v[18:19], v[6:7], off offset:768
	global_load_dwordx2 v[20:21], v[6:7], off offset:1024
	global_load_dwordx2 v[22:23], v[6:7], off offset:1280
	global_load_dwordx2 v[24:25], v[6:7], off offset:1536
	global_load_dwordx2 v[26:27], v[6:7], off offset:1792
	global_load_dwordx4 v[0:3], v[34:35], off
	v_lshlrev_b64 v[28:29], 2, v[4:5]
	v_lshl_add_u64 v[30:31], s[12:13], 0, v[28:29]
	global_load_dwordx4 v[8:11], v[30:31], off
	s_waitcnt vmcnt(18)
	v_lshl_add_u64 v[98:99], s[14:15], 0, v[28:29]
	v_lshl_add_u64 v[40:41], s[8:9], 0, v[40:41]
	v_add_u32_e32 v33, s56, v33
	v_add_u32_e32 v38, s26, v38
	s_waitcnt vmcnt(9)
	v_lshlrev_b32_e32 v70, 16, v12
	v_and_b32_e32 v71, 0xffff0000, v12
	s_waitcnt vmcnt(8)
	v_lshlrev_b32_e32 v74, 16, v14
	v_and_b32_e32 v75, 0xffff0000, v14
	s_waitcnt vmcnt(7)
	v_and_b32_e32 v79, 0xffff0000, v16
	s_waitcnt vmcnt(6)
	v_and_b32_e32 v83, 0xffff0000, v18
	v_lshlrev_b32_e32 v72, 16, v13
	v_and_b32_e32 v73, 0xffff0000, v13
	v_lshlrev_b32_e32 v76, 16, v15
	v_and_b32_e32 v77, 0xffff0000, v15
	v_lshlrev_b32_e32 v78, 16, v16
	v_lshlrev_b32_e32 v80, 16, v17
	v_and_b32_e32 v81, 0xffff0000, v17
	v_lshlrev_b32_e32 v82, 16, v18
	s_waitcnt vmcnt(4)
	v_lshlrev_b32_e32 v90, 16, v22
	v_and_b32_e32 v91, 0xffff0000, v22
	v_lshlrev_b32_e32 v92, 16, v23
	v_and_b32_e32 v93, 0xffff0000, v23
	v_pk_mul_f32 v[12:13], v[70:71], v[70:71]
	v_pk_mul_f32 v[16:17], v[74:75], v[74:75]
	v_mov_b32_e32 v22, v79
	v_mov_b32_e32 v23, v83
	v_lshlrev_b32_e32 v84, 16, v19
	v_and_b32_e32 v85, 0xffff0000, v19
	v_lshlrev_b32_e32 v86, 16, v20
	v_and_b32_e32 v87, 0xffff0000, v20
	v_lshlrev_b32_e32 v88, 16, v21
	v_and_b32_e32 v89, 0xffff0000, v21
	v_pk_mul_f32 v[14:15], v[72:73], v[72:73]
	v_pk_mul_f32 v[18:19], v[76:77], v[76:77]
	v_mov_b32_e32 v20, v78
	v_mov_b32_e32 v21, v82
	v_pk_mul_f32 v[22:23], v[22:23], v[22:23]
	v_add_f32_e32 v39, v16, v17
	v_add_f32_e32 v12, v12, v13
	s_waitcnt vmcnt(3)
	v_lshlrev_b32_e32 v94, 16, v24
	v_and_b32_e32 v95, 0xffff0000, v24
	v_lshlrev_b32_e32 v96, 16, v25
	v_and_b32_e32 v97, 0xffff0000, v25
	v_mov_b32_e32 v24, v80
	v_mov_b32_e32 v25, v84
	v_mov_b32_e32 v52, v87
	v_mov_b32_e32 v53, v91
	v_pk_fma_f32 v[16:17], v[20:21], v[20:21], v[22:23]
	v_add_f32_e32 v18, v39, v18
	v_add_f32_e32 v12, v12, v14
	s_waitcnt vmcnt(2)
	v_lshlrev_b32_e32 v6, 16, v26
	v_and_b32_e32 v7, 0xffff0000, v26
	v_lshlrev_b32_e32 v4, 16, v27
	v_and_b32_e32 v5, 0xffff0000, v27
	v_mov_b32_e32 v26, v81
	v_mov_b32_e32 v27, v85
	v_mov_b32_e32 v50, v86
	v_mov_b32_e32 v51, v90
	v_pk_mul_f32 v[52:53], v[52:53], v[52:53]
	v_pk_fma_f32 v[16:17], v[24:25], v[24:25], v[16:17]
	v_add_f32_e32 v18, v19, v18
	v_add_f32_e32 v12, v15, v12
	v_mov_b32_e32 v54, v88
	v_mov_b32_e32 v55, v92
	v_mov_b32_e32 v60, v95
	v_mov_b32_e32 v61, v7
	v_pk_fma_f32 v[20:21], v[50:51], v[50:51], v[52:53]
	v_pk_fma_f32 v[16:17], v[26:27], v[26:27], v[16:17]
	v_add_f32_e32 v12, v12, v18
	v_mov_b32_e32 v56, v89
	v_mov_b32_e32 v57, v93
	v_mov_b32_e32 v58, v94
	v_mov_b32_e32 v59, v6
	v_pk_mul_f32 v[60:61], v[60:61], v[60:61]
	v_pk_fma_f32 v[20:21], v[54:55], v[54:55], v[20:21]
	v_add_f32_e32 v12, v12, v16
	v_mov_b32_e32 v62, v96
	v_mov_b32_e32 v63, v4
	v_pk_fma_f32 v[22:23], v[58:59], v[58:59], v[60:61]
	v_pk_fma_f32 v[20:21], v[56:57], v[56:57], v[20:21]
	v_add_f32_e32 v12, v12, v17
	v_mov_b32_e32 v64, v97
	v_mov_b32_e32 v65, v5
	v_pk_fma_f32 v[22:23], v[62:63], v[62:63], v[22:23]
	v_add_f32_e32 v12, v12, v20
	v_pk_fma_f32 v[22:23], v[64:65], v[64:65], v[22:23]
	v_add_f32_e32 v12, v12, v21
	v_add_f32_e32 v12, v12, v22
	v_add_f32_e32 v12, v12, v23
	ds_bpermute_b32 v13, v42, v12
	s_waitcnt lgkmcnt(0)
	v_add_f32_e32 v12, v12, v13
	ds_bpermute_b32 v13, v43, v12
	s_waitcnt lgkmcnt(0)
	v_add_f32_e32 v12, v12, v13
	ds_bpermute_b32 v13, v44, v12
	s_waitcnt lgkmcnt(0)
	v_add_f32_e32 v12, v12, v13
	ds_bpermute_b32 v13, v45, v12
	s_waitcnt lgkmcnt(0)
	v_add_f32_e32 v20, v12, v13
	ds_bpermute_b32 v21, v46, v20
	global_load_dwordx4 v[12:15], v[30:31], off offset:512
	global_load_dwordx4 v[16:19], v[30:31], off offset:1024
	global_load_dwordx4 v[50:53], v[30:31], off offset:1536
	global_load_dwordx4 v[54:57], v[30:31], off offset:2048
	global_load_dwordx4 v[58:61], v[30:31], off offset:2560
	global_load_dwordx4 v[62:65], v[30:31], off offset:3072
	global_load_dwordx4 v[66:69], v[30:31], off offset:3584
	s_waitcnt lgkmcnt(0)
	v_add_f32_e32 v20, v20, v21
	v_fmamk_f32 v20, v20, 0x3a800000, v47
	v_mul_f32_e32 v21, 0x4b800000, v20
	v_cmp_gt_f32_e32 vcc, s27, v20
	s_nop 1
	v_cndmask_b32_e32 v20, v20, v21, vcc
	v_rsq_f32_e32 v20, v20
	s_nop 0
	v_mul_f32_e32 v21, 0x45800000, v20
	v_cndmask_b32_e32 v100, v20, v21, vcc
	v_pk_mul_f32 v[20:21], v[100:101], v[70:71] op_sel_hi:[0,1]
	v_pk_mul_f32 v[22:23], v[100:101], v[72:73] op_sel_hi:[0,1]
	s_waitcnt vmcnt(7)
	v_pk_fma_f32 v[28:29], v[0:1], v[20:21], v[8:9]
	v_pk_fma_f32 v[30:31], v[2:3], v[22:23], v[10:11]
	global_store_dwordx4 v[98:99], v[28:31], off
	global_load_dwordx4 v[0:3], v[34:35], off offset:512
	v_pk_mul_f32 v[8:9], v[100:101], v[74:75] op_sel_hi:[0,1]
	v_pk_mul_f32 v[10:11], v[100:101], v[76:77] op_sel_hi:[0,1]
	v_pk_mul_f32 v[6:7], v[100:101], v[6:7] op_sel_hi:[0,1]
	s_waitcnt vmcnt(0)
; __device__ __forceinline__ unsigned pack2(float a, float b) { return (unsigned)f2bf(a) | ((unsigned)f2bf(b) << 16); }
; __device__ void norm_phase(const Params& p, int layer) {
;     ...
;       for (int i = 0; i < 8; ++i) {
;         float4 g = *reinterpret_cast<const float4*>(p.g_post + (size_t)layer * DM + l32 * 4 + i * 128);
;         xv[i].x += ov[i].x * rstd * g.x;
;         xv[i].y += ov[i].y * rstd * g.y;
;         xv[i].z += ov[i].z * rstd * g.z;
;         xv[i].w += ov[i].w * rstd * g.w;
;         *reinterpret_cast<float4*>(p.out + rbase + i * 128) = xv[i];
;       }
;     }
;     const int nl = layer + 1;
;     if (nl < 4) {
;       float ss = 0.f;
; #pragma unroll
;       for (int i = 0; i < 8; ++i) ss += xv[i].x * xv[i].x + xv[i].y * xv[i].y + xv[i].z * xv[i].z + xv[i].w * xv[i].w;
;       ss = half_wave_sum(ss);
;       float rstd = rsqrtf(ss * (1.f / 1024.f) + 1e-6f);
; #pragma unroll
;       for (int i = 0; i < 8; ++i) {
;         float4 g = *reinterpret_cast<const float4*>(p.g_pre + (size_t)nl * DM + l32 * 4 + i * 128);
;         uint2 o;
;         o.x = pack2(xv[i].x * rstd * g.x, xv[i].y * rstd * g.y);
;         o.y = pack2(xv[i].z * rstd * g.z, xv[i].w * rstd * g.w);
;         *reinterpret_cast<uint2*>(H + rbase + i * 128) = o;
;       }
	v_pk_fma_f32 v[24:25], v[8:9], v[0:1], v[12:13]
	v_pk_fma_f32 v[26:27], v[10:11], v[2:3], v[14:15]
	global_store_dwordx4 v[98:99], v[24:27], off offset:512
	global_load_dwordx4 v[0:3], v[34:35], off offset:1024
	v_pk_mul_f32 v[8:9], v[100:101], v[78:79] op_sel_hi:[0,1]
	v_pk_mul_f32 v[10:11], v[100:101], v[80:81] op_sel_hi:[0,1]
	s_waitcnt vmcnt(0)
	v_pk_fma_f32 v[20:21], v[8:9], v[0:1], v[16:17]
	v_pk_fma_f32 v[22:23], v[10:11], v[2:3], v[18:19]
	global_store_dwordx4 v[98:99], v[20:23], off offset:1024
	global_load_dwordx4 v[0:3], v[34:35], off offset:1536
	v_pk_mul_f32 v[8:9], v[100:101], v[82:83] op_sel_hi:[0,1]
	v_pk_mul_f32 v[10:11], v[100:101], v[84:85] op_sel_hi:[0,1]
	s_waitcnt vmcnt(0)
	v_pk_fma_f32 v[16:17], v[8:9], v[0:1], v[50:51]
	v_pk_fma_f32 v[18:19], v[10:11], v[2:3], v[52:53]
	global_store_dwordx4 v[98:99], v[16:19], off offset:1536
	global_load_dwordx4 v[0:3], v[34:35], off offset:2048
	v_pk_mul_f32 v[8:9], v[100:101], v[86:87] op_sel_hi:[0,1]
	v_pk_mul_f32 v[10:11], v[100:101], v[88:89] op_sel_hi:[0,1]
	v_pk_mul_f32 v[50:51], v[100:101], v[94:95] op_sel_hi:[0,1]
	v_pk_mul_f32 v[52:53], v[100:101], v[96:97] op_sel_hi:[0,1]
	s_waitcnt vmcnt(0)
	v_pk_fma_f32 v[12:13], v[8:9], v[0:1], v[54:55]
	v_pk_fma_f32 v[14:15], v[10:11], v[2:3], v[56:57]
	global_store_dwordx4 v[98:99], v[12:15], off offset:2048
	global_load_dwordx4 v[0:3], v[34:35], off offset:2560
	v_pk_mul_f32 v[8:9], v[100:101], v[90:91] op_sel_hi:[0,1]
	v_pk_mul_f32 v[10:11], v[100:101], v[92:93] op_sel_hi:[0,1]
	v_pk_mul_f32 v[54:55], v[100:101], v[4:5] op_sel_hi:[0,1]
	v_pk_mul_f32 v[4:5], v[28:29], v[28:29]
	v_pk_mul_f32 v[56:57], v[30:31], v[30:31]
	v_add_f32_e32 v4, v4, v5
	v_add_f32_e32 v4, v56, v4
	v_add_f32_e32 v39, v57, v4
	v_pk_mul_f32 v[4:5], v[24:25], v[24:25]
	v_pk_mul_f32 v[56:57], v[26:27], v[26:27]
	v_add_f32_e32 v4, v4, v5
	v_add_f32_e32 v4, v4, v56
	v_add_f32_e32 v4, v4, v57
	v_add_f32_e32 v39, v39, v4
	v_mov_b32_e32 v56, v20
	v_mov_b32_e32 v57, v16
	s_waitcnt vmcnt(0)
	v_pk_fma_f32 v[8:9], v[8:9], v[0:1], v[58:59]
	v_pk_fma_f32 v[10:11], v[10:11], v[2:3], v[60:61]
	global_store_dwordx4 v[98:99], v[8:11], off offset:2560
	global_load_dwordx4 v[0:3], v[34:35], off offset:3072
	v_mov_b32_e32 v58, v21
	v_mov_b32_e32 v59, v17
	v_mov_b32_e32 v60, v22
	v_mov_b32_e32 v61, v18
	s_waitcnt vmcnt(0)
	v_pk_fma_f32 v[0:1], v[50:51], v[0:1], v[62:63]
	v_pk_fma_f32 v[2:3], v[52:53], v[2:3], v[64:65]
	global_store_dwordx4 v[98:99], v[0:3], off offset:3072
	global_load_dwordx4 v[50:53], v[34:35], off offset:3584
	v_mov_b32_e32 v62, v23
	v_mov_b32_e32 v63, v19
	s_waitcnt vmcnt(0)
	v_pk_fma_f32 v[4:5], v[6:7], v[50:51], v[66:67]
	v_pk_fma_f32 v[6:7], v[54:55], v[52:53], v[68:69]
	global_store_dwordx4 v[98:99], v[4:7], off offset:3584
	global_load_dwordx4 v[50:53], v[36:37], off
	v_pk_mul_f32 v[54:55], v[58:59], v[58:59]
	v_mov_b32_e32 v58, v14
	v_pk_fma_f32 v[54:55], v[56:57], v[56:57], v[54:55]
	v_mov_b32_e32 v56, v13
	v_pk_fma_f32 v[54:55], v[60:61], v[60:61], v[54:55]
	v_mov_b32_e32 v57, v9
	v_pk_fma_f32 v[54:55], v[62:63], v[62:63], v[54:55]
	v_pk_mul_f32 v[56:57], v[56:57], v[56:57]
	v_add_f32_e32 v39, v39, v54
	v_add_f32_e32 v39, v39, v55
	v_mov_b32_e32 v54, v12
	v_mov_b32_e32 v55, v8
	v_mov_b32_e32 v59, v10
	v_pk_fma_f32 v[54:55], v[54:55], v[54:55], v[56:57]
	v_mov_b32_e32 v60, v15
	v_mov_b32_e32 v61, v11
	v_pk_fma_f32 v[54:55], v[58:59], v[58:59], v[54:55]
	v_mov_b32_e32 v56, v1
	v_pk_fma_f32 v[54:55], v[60:61], v[60:61], v[54:55]
	v_mov_b32_e32 v57, v5
	v_add_f32_e32 v39, v39, v54
	v_add_f32_e32 v39, v39, v55
	v_mov_b32_e32 v54, v0
	v_mov_b32_e32 v55, v4
	v_pk_mul_f32 v[56:57], v[56:57], v[56:57]
	v_mov_b32_e32 v58, v2
	v_mov_b32_e32 v59, v6
	v_pk_fma_f32 v[54:55], v[54:55], v[54:55], v[56:57]
	v_mov_b32_e32 v60, v3
	v_mov_b32_e32 v61, v7
	v_pk_fma_f32 v[54:55], v[58:59], v[58:59], v[54:55]
	s_waitcnt vmcnt(0)
	v_mov_b32_e32 v57, v52
	v_pk_fma_f32 v[54:55], v[60:61], v[60:61], v[54:55]
	v_mov_b32_e32 v52, v51
	v_add_f32_e32 v39, v39, v54
	v_add_f32_e32 v39, v39, v55
	ds_bpermute_b32 v49, v42, v39
	v_mov_b32_e32 v54, v28
	v_mov_b32_e32 v55, v30
	v_mov_b32_e32 v30, v29
	v_mov_b32_e32 v56, v50
	s_waitcnt lgkmcnt(0)
	v_add_f32_e32 v39, v39, v49
	ds_bpermute_b32 v49, v43, v39
	s_waitcnt lgkmcnt(0)
	v_add_f32_e32 v39, v39, v49
	ds_bpermute_b32 v49, v44, v39
	s_waitcnt lgkmcnt(0)
	v_add_f32_e32 v39, v39, v49
	ds_bpermute_b32 v49, v45, v39
	s_waitcnt lgkmcnt(0)
	v_add_f32_e32 v39, v39, v49
	ds_bpermute_b32 v49, v46, v39
	s_waitcnt lgkmcnt(0)
	v_add_f32_e32 v39, v39, v49
	v_fmamk_f32 v39, v39, 0x3a800000, v47
	v_mul_f32_e32 v49, 0x4b800000, v39
	v_cmp_gt_f32_e32 vcc, s27, v39
	s_nop 1
	v_cndmask_b32_e32 v39, v39, v49, vcc
	v_rsq_f32_e32 v39, v39
	s_nop 0
	v_mul_f32_e32 v28, 0x45800000, v39
	v_cndmask_b32_e32 v28, v39, v28, vcc
	v_pk_mul_f32 v[30:31], v[30:31], v[28:29] op_sel_hi:[1,0]
	v_pk_mul_f32 v[54:55], v[54:55], v[28:29] op_sel_hi:[1,0]
	v_pk_mul_f32 v[30:31], v[52:53], v[30:31]
	v_pk_mul_f32 v[50:51], v[56:57], v[54:55]
	v_cvt_pk_bf16_f32 v31, 0, v31
	v_cvt_pk_bf16_f32 v30, 0, v30
	v_cvt_pk_bf16_f32 v39, 0, v50
	v_cvt_pk_bf16_f32 v29, 0, v51
	v_and_b32_e32 v31, 0xffff0000, v31
	v_and_b32_e32 v30, 0xffff0000, v30
	v_or_b32_sdwa v31, v31, v29 dst_sel:DWORD dst_unused:UNUSED_PAD src0_sel:DWORD src1_sel:WORD_1
	v_or_b32_sdwa v30, v30, v39 dst_sel:DWORD dst_unused:UNUSED_PAD src0_sel:DWORD src1_sel:WORD_1
	global_store_dwordx2 v[40:41], v[30:31], off
	global_load_dwordx4 v[50:53], v[36:37], off offset:512
	v_mov_b32_e32 v30, v24
	v_mov_b32_e32 v31, v26
	v_mov_b32_e32 v26, v25
	v_pk_mul_f32 v[24:25], v[30:31], v[28:29] op_sel_hi:[1,0]
	v_pk_mul_f32 v[26:27], v[26:27], v[28:29] op_sel_hi:[1,0]
	v_cmp_lt_i32_e32 vcc, s37, v33
	s_or_b64 s[24:25], vcc, s[24:25]
	s_waitcnt vmcnt(0)
; __device__ __forceinline__ unsigned pack2(float a, float b) { return (unsigned)f2bf(a) | ((unsigned)f2bf(b) << 16); }
; __device__ void norm_phase(const Params& p, int layer) {
;     ...
; #pragma unroll
;       for (int i = 0; i < 8; ++i) {
;         float4 g = *reinterpret_cast<const float4*>(p.g_pre + (size_t)nl * DM + l32 * 4 + i * 128);
;         uint2 o;
;         o.x = pack2(xv[i].x * rstd * g.x, xv[i].y * rstd * g.y);
;         o.y = pack2(xv[i].z * rstd * g.z, xv[i].w * rstd * g.w);
;         *reinterpret_cast<uint2*>(H + rbase + i * 128) = o;
;       }
	v_mov_b32_e32 v31, v52
	v_mov_b32_e32 v52, v51
	v_mov_b32_e32 v30, v50
	v_pk_mul_f32 v[26:27], v[52:53], v[26:27]
	v_pk_mul_f32 v[24:25], v[30:31], v[24:25]
	v_and_b32_sdwa v29, v25, v48 dst_sel:DWORD dst_unused:UNUSED_PAD src0_sel:WORD_1 src1_sel:DWORD
	v_cvt_pk_bf16_f32 v27, 0, v27
	v_cvt_pk_bf16_f32 v26, 0, v26
	v_cvt_pk_bf16_f32 v24, 0, v24
	v_cvt_pk_bf16_f32 v25, 0, v25
	v_and_b32_e32 v27, 0xffff0000, v27
	v_and_b32_e32 v26, 0xffff0000, v26
	v_or_b32_sdwa v25, v27, v25 dst_sel:DWORD dst_unused:UNUSED_PAD src0_sel:DWORD src1_sel:WORD_1
	v_or_b32_sdwa v24, v26, v24 dst_sel:DWORD dst_unused:UNUSED_PAD src0_sel:DWORD src1_sel:WORD_1
	global_store_dwordx2 v[40:41], v[24:25], off offset:256
	global_load_dwordx4 v[24:27], v[36:37], off offset:1024
	v_mov_b32_e32 v30, v20
	v_mov_b32_e32 v31, v22
	v_mov_b32_e32 v22, v21
	v_pk_mul_f32 v[20:21], v[30:31], v[28:29] op_sel_hi:[1,0]
	v_pk_mul_f32 v[22:23], v[22:23], v[28:29] op_sel_hi:[1,0]
	s_waitcnt vmcnt(0)
	v_mov_b32_e32 v31, v26
	v_mov_b32_e32 v26, v25
	v_mov_b32_e32 v30, v24
	v_pk_mul_f32 v[22:23], v[22:23], v[26:27]
	v_pk_mul_f32 v[20:21], v[20:21], v[30:31]
	v_cvt_pk_bf16_f32 v23, 0, v23
	v_cvt_pk_bf16_f32 v22, 0, v22
	v_cvt_pk_bf16_f32 v20, 0, v20
	v_cvt_pk_bf16_f32 v21, 0, v21
	v_and_b32_e32 v23, 0xffff0000, v23
	v_and_b32_e32 v22, 0xffff0000, v22
	v_or_b32_sdwa v21, v23, v21 dst_sel:DWORD dst_unused:UNUSED_PAD src0_sel:DWORD src1_sel:WORD_1
	v_or_b32_sdwa v20, v22, v20 dst_sel:DWORD dst_unused:UNUSED_PAD src0_sel:DWORD src1_sel:WORD_1
	global_store_dwordx2 v[40:41], v[20:21], off offset:512
	global_load_dwordx4 v[20:23], v[36:37], off offset:1536
	v_mov_b32_e32 v24, v16
	v_mov_b32_e32 v25, v18
	v_mov_b32_e32 v18, v17
	v_pk_mul_f32 v[16:17], v[24:25], v[28:29] op_sel_hi:[1,0]
	v_pk_mul_f32 v[18:19], v[18:19], v[28:29] op_sel_hi:[1,0]
	s_waitcnt vmcnt(0)
	v_mov_b32_e32 v25, v22
	v_mov_b32_e32 v22, v21
	v_mov_b32_e32 v24, v20
	v_pk_mul_f32 v[18:19], v[18:19], v[22:23]
	v_pk_mul_f32 v[16:17], v[16:17], v[24:25]
	v_cvt_pk_bf16_f32 v19, 0, v19
	v_cvt_pk_bf16_f32 v18, 0, v18
	v_cvt_pk_bf16_f32 v16, 0, v16
	v_cvt_pk_bf16_f32 v17, 0, v17
	v_and_b32_e32 v19, 0xffff0000, v19
	v_and_b32_e32 v18, 0xffff0000, v18
	v_or_b32_sdwa v17, v19, v17 dst_sel:DWORD dst_unused:UNUSED_PAD src0_sel:DWORD src1_sel:WORD_1
	v_or_b32_sdwa v16, v18, v16 dst_sel:DWORD dst_unused:UNUSED_PAD src0_sel:DWORD src1_sel:WORD_1
	global_store_dwordx2 v[40:41], v[16:17], off offset:768
	global_load_dwordx4 v[16:19], v[36:37], off offset:2048
	v_mov_b32_e32 v20, v12
	v_mov_b32_e32 v21, v14
	v_mov_b32_e32 v14, v13
	v_pk_mul_f32 v[12:13], v[20:21], v[28:29] op_sel_hi:[1,0]
	v_pk_mul_f32 v[14:15], v[14:15], v[28:29] op_sel_hi:[1,0]
	s_waitcnt vmcnt(0)
	v_mov_b32_e32 v21, v18
	v_mov_b32_e32 v18, v17
	v_mov_b32_e32 v20, v16
	v_pk_mul_f32 v[14:15], v[14:15], v[18:19]
	v_pk_mul_f32 v[12:13], v[12:13], v[20:21]
	v_cvt_pk_bf16_f32 v15, 0, v15
	v_cvt_pk_bf16_f32 v14, 0, v14
	v_cvt_pk_bf16_f32 v12, 0, v12
	v_cvt_pk_bf16_f32 v13, 0, v13
	v_and_b32_e32 v15, 0xffff0000, v15
	v_and_b32_e32 v14, 0xffff0000, v14
	v_or_b32_sdwa v13, v15, v13 dst_sel:DWORD dst_unused:UNUSED_PAD src0_sel:DWORD src1_sel:WORD_1
	v_or_b32_sdwa v12, v14, v12 dst_sel:DWORD dst_unused:UNUSED_PAD src0_sel:DWORD src1_sel:WORD_1
	global_store_dwordx2 v[40:41], v[12:13], off offset:1024
	global_load_dwordx4 v[12:15], v[36:37], off offset:2560
	v_mov_b32_e32 v16, v8
	v_mov_b32_e32 v17, v10
	v_mov_b32_e32 v10, v9
	v_pk_mul_f32 v[8:9], v[16:17], v[28:29] op_sel_hi:[1,0]
	v_pk_mul_f32 v[10:11], v[10:11], v[28:29] op_sel_hi:[1,0]
	s_waitcnt vmcnt(0)
	v_mov_b32_e32 v17, v14
	v_mov_b32_e32 v14, v13
	v_mov_b32_e32 v16, v12
	v_pk_mul_f32 v[10:11], v[10:11], v[14:15]
	v_pk_mul_f32 v[8:9], v[8:9], v[16:17]
	v_and_b32_sdwa v14, v11, v48 dst_sel:DWORD dst_unused:UNUSED_PAD src0_sel:WORD_1 src1_sel:DWORD
	v_and_b32_sdwa v15, v10, v48 dst_sel:DWORD dst_unused:UNUSED_PAD src0_sel:WORD_1 src1_sel:DWORD
	v_cvt_pk_bf16_f32 v11, 0, v11
	v_cvt_pk_bf16_f32 v10, 0, v10
	v_cvt_pk_bf16_f32 v8, 0, v8
	v_cvt_pk_bf16_f32 v9, 0, v9
	v_and_b32_e32 v11, 0xffff0000, v11
	v_and_b32_e32 v10, 0xffff0000, v10
	v_or_b32_sdwa v9, v11, v9 dst_sel:DWORD dst_unused:UNUSED_PAD src0_sel:DWORD src1_sel:WORD_1
	v_or_b32_sdwa v8, v10, v8 dst_sel:DWORD dst_unused:UNUSED_PAD src0_sel:DWORD src1_sel:WORD_1
	global_store_dwordx2 v[40:41], v[8:9], off offset:1280
	global_load_dwordx4 v[8:11], v[36:37], off offset:3072
	v_mov_b32_e32 v12, v0
	v_mov_b32_e32 v13, v2
	v_mov_b32_e32 v2, v1
	v_pk_mul_f32 v[0:1], v[12:13], v[28:29] op_sel_hi:[1,0]
	v_pk_mul_f32 v[2:3], v[2:3], v[28:29] op_sel_hi:[1,0]
	s_waitcnt vmcnt(0)
	v_mov_b32_e32 v13, v10
	v_mov_b32_e32 v10, v9
	v_mov_b32_e32 v12, v8
	v_pk_mul_f32 v[2:3], v[2:3], v[10:11]
	v_pk_mul_f32 v[0:1], v[0:1], v[12:13]
	v_cvt_pk_bf16_f32 v3, 0, v3
	v_cvt_pk_bf16_f32 v2, 0, v2
	v_cvt_pk_bf16_f32 v0, 0, v0
	v_cvt_pk_bf16_f32 v1, 0, v1
	v_and_b32_e32 v3, 0xffff0000, v3
	v_and_b32_e32 v2, 0xffff0000, v2
	v_or_b32_sdwa v1, v3, v1 dst_sel:DWORD dst_unused:UNUSED_PAD src0_sel:DWORD src1_sel:WORD_1
	v_or_b32_sdwa v0, v2, v0 dst_sel:DWORD dst_unused:UNUSED_PAD src0_sel:DWORD src1_sel:WORD_1
	global_store_dwordx2 v[40:41], v[0:1], off offset:1536
	global_load_dwordx4 v[0:3], v[36:37], off offset:3584
	v_mov_b32_e32 v8, v4
	v_mov_b32_e32 v9, v6
	v_mov_b32_e32 v6, v5
	v_pk_mul_f32 v[4:5], v[8:9], v[28:29] op_sel_hi:[1,0]
	v_pk_mul_f32 v[6:7], v[6:7], v[28:29] op_sel_hi:[1,0]
	s_waitcnt vmcnt(0)
	v_mov_b32_e32 v9, v2
	v_mov_b32_e32 v2, v1
	v_mov_b32_e32 v8, v0
	v_pk_mul_f32 v[2:3], v[6:7], v[2:3]
	v_pk_mul_f32 v[0:1], v[4:5], v[8:9]
	v_cvt_pk_bf16_f32 v3, 0, v3
	v_cvt_pk_bf16_f32 v2, 0, v2
	v_cvt_pk_bf16_f32 v0, 0, v0
	v_cvt_pk_bf16_f32 v1, 0, v1
	v_and_b32_e32 v3, 0xffff0000, v3
	v_and_b32_e32 v2, 0xffff0000, v2
	v_or_b32_sdwa v1, v3, v1 dst_sel:DWORD dst_unused:UNUSED_PAD src0_sel:DWORD src1_sel:WORD_1
	v_or_b32_sdwa v0, v2, v0 dst_sel:DWORD dst_unused:UNUSED_PAD src0_sel:DWORD src1_sel:WORD_1
	global_store_dwordx2 v[40:41], v[0:1], off offset:1792
	s_andn2_b64 exec, exec, s[24:25]
	s_cbranch_execnz .LBB0_359
	s_or_b64 exec, exec, s[24:25]
	v_mov_b64_e32 v[10:11], s[28:29]

; __device__ void convert_weights(const Params& p, int layer, char* smem) {
;     ...
;       for (int e = tid; e < 4096; e += 256) {
;         int idx = v * 4096 + e;
;         int t = (idx >> 7) & 127, s = idx & 127;
;         float w = p.gm_w_s[(size_t)layer * 65536 + idx];
;         Ws_bf[idx] = (s <= t) ? f2bf(w) : (u16)0;
;       }
.LBB0_370:
	v_add_u32_e32 v13, s46, v9
	v_bfe_u32 v13, v13, 7, 7
	v_cmp_le_u32_e32 vcc, v21, v13
	v_mov_b32_e32 v13, 0
	s_and_saveexec_b64 s[40:41], vcc
	s_cbranch_execz .LBB0_369
	global_load_dword v13, v[14:15], off
	s_waitcnt vmcnt(0)
	v_cvt_pk_bf16_f32 v13, 0, v13
	v_lshrrev_b32_e32 v13, 16, v13
	s_branch .LBB0_369

; __device__ __forceinline__ unsigned pack2(float a, float b) { return (unsigned)f2bf(a) | ((unsigned)f2bf(b) << 16); }
; __device__ void convert_weights(const Params& p, int layer, char* smem) {
;     ...
;     __syncthreads();
; #pragma unroll
;     for (int i = 0; i < 4; ++i) {
;       int kk = (tid >> 4) + 16 * i, nn = (tid & 15) * 4;
;       float4 v = *reinterpret_cast<const float4*>(src + (size_t)(kt * 64 + kk) * N + nt * 64 + nn);
;       tile[kk * 65 + nn + 0] = v.x; tile[kk * 65 + nn + 1] = v.y;
;       tile[kk * 65 + nn + 2] = v.z; tile[kk * 65 + nn + 3] = v.w;
;     }
;     __syncthreads();
; #pragma unroll
;     for (int i = 0; i < 2; ++i) {
;       int nn = (tid >> 3) + 32 * i, kk0 = (tid & 7) * 8;
;       uint4 o;
;       o.x = pack2(tile[(kk0 + 0) * 65 + nn], tile[(kk0 + 1) * 65 + nn]);
;       o.y = pack2(tile[(kk0 + 2) * 65 + nn], tile[(kk0 + 3) * 65 + nn]);
;       o.z = pack2(tile[(kk0 + 4) * 65 + nn], tile[(kk0 + 5) * 65 + nn]);
;       o.w = pack2(tile[(kk0 + 6) * 65 + nn], tile[(kk0 + 7) * 65 + nn]);
;       *reinterpret_cast<uint4*>(dst + (size_t)(nt * 64 + nn) * K + kt * 64 + kk0) = o;
;     }
.LBB0_381:
	s_andn2_b64 vcc, exec, s[38:39]
	s_cbranch_vccnz .LBB0_363
	s_lshl_b32 s44, s53, 6
	s_ashr_i32 s45, s44, 31
	s_lshl_b32 s38, s52, 6
	s_lshl_b64 s[52:53], s[44:45], 2
	s_add_u32 s40, s40, s52
	v_add_u32_e32 v9, s38, v19
	s_addc_u32 s41, s41, s53
	v_add_u32_e32 v13, 16, v9
	v_lshl_add_u64 v[16:17], s[40:41], 0, v[0:1]
	v_mad_i64_i32 v[32:33], s[40:41], s42, v9, 0
	v_mad_i64_i32 v[34:35], s[40:41], s42, v13, 0
	v_lshl_add_u64 v[32:33], v[32:33], 2, v[16:17]
	v_lshl_add_u64 v[36:37], v[34:35], 2, v[16:17]
	s_barrier
	global_load_dwordx4 v[32:35], v[32:33], off
	s_nop 0
	global_load_dwordx4 v[36:39], v[36:37], off
	v_add_u32_e32 v13, 32, v9
	v_mad_i64_i32 v[40:41], s[40:41], s42, v13, 0
	v_lshl_add_u64 v[40:41], v[40:41], 2, v[16:17]
	v_add_u32_e32 v9, 48, v9
	global_load_dwordx4 v[40:43], v[40:41], off
	v_mad_i64_i32 v[44:45], s[40:41], s42, v9, 0
	v_lshl_add_u64 v[16:17], v[44:45], 2, v[16:17]
	global_load_dwordx4 v[44:47], v[16:17], off
	v_add_u32_e32 v9, s44, v20
	v_ashrrev_i32_e32 v48, 31, v9
	v_mul_lo_u32 v50, s37, v9
	v_mad_u64_u32 v[16:17], s[40:41], s36, v9, 0
	v_add_u32_e32 v9, 32, v9
	v_ashrrev_i32_e32 v52, 31, v9
	s_ashr_i32 s39, s38, 31
	v_mov_b32_e32 v13, v1
	v_mul_lo_u32 v51, s36, v48
	v_mul_lo_u32 v53, s37, v9
	v_mad_u64_u32 v[48:49], s[40:41], s36, v9, 0
	v_mul_lo_u32 v9, s36, v52
	v_lshl_add_u64 v[14:15], s[38:39], 1, v[14:15]
	v_add3_u32 v17, v17, v51, v50
	v_add3_u32 v49, v49, v9, v53
	v_lshl_add_u64 v[14:15], v[14:15], 0, v[12:13]
	v_lshl_add_u64 v[50:51], v[16:17], 1, v[14:15]
	v_lshl_add_u64 v[48:49], v[48:49], 1, v[14:15]
	s_waitcnt vmcnt(3)
	ds_write2_b32 v23, v32, v33 offset1:1
	ds_write2_b32 v23, v34, v35 offset0:2 offset1:3
	s_waitcnt vmcnt(2)
	ds_write2_b32 v24, v36, v37 offset1:1
	ds_write2_b32 v25, v38, v39 offset1:1
	s_waitcnt vmcnt(1)
	ds_write2_b32 v26, v40, v41 offset1:1
	ds_write2_b32 v27, v42, v43 offset1:1
	s_waitcnt vmcnt(0)
	ds_write2_b32 v28, v44, v45 offset1:1
	ds_write2_b32 v29, v46, v47 offset1:1
	s_waitcnt lgkmcnt(0)
	s_barrier
	ds_read2_b32 v[14:15], v22 offset1:32
	ds_read2_b32 v[32:33], v22 offset0:65 offset1:97
	ds_read2_b32 v[34:35], v22 offset0:130 offset1:162
	ds_read2_b32 v[36:37], v22 offset0:195 offset1:227
	ds_read2_b32 v[38:39], v30 offset0:4 offset1:36
	ds_read2_b32 v[40:41], v30 offset0:69 offset1:101
	ds_read2_b32 v[42:43], v30 offset0:134 offset1:166
	ds_read2_b32 v[44:45], v30 offset0:199 offset1:231
	s_waitcnt lgkmcnt(7)
	s_waitcnt lgkmcnt(4)
	s_waitcnt lgkmcnt(0)
	v_cvt_pk_bf16_f32 v13, 0, v14
	v_cvt_pk_bf16_f32 v14, 0, v36
	v_cvt_pk_bf16_f32 v16, 0, v32
	v_cvt_pk_bf16_f32 v9, 0, v34
	v_cvt_pk_bf16_f32 v34, 0, v44
	v_cvt_pk_bf16_f32 v36, 0, v40
	v_and_b32_e32 v14, 0xffff0000, v14
	v_and_b32_e32 v16, 0xffff0000, v16
	v_cvt_pk_bf16_f32 v32, 0, v38
	v_cvt_pk_bf16_f32 v17, 0, v42
	v_cvt_pk_bf16_f32 v38, 0, v15
	v_and_b32_e32 v34, 0xffff0000, v34
	v_and_b32_e32 v36, 0xffff0000, v36
	v_or_b32_sdwa v15, v14, v9 dst_sel:DWORD dst_unused:UNUSED_PAD src0_sel:DWORD src1_sel:WORD_1
	v_or_b32_sdwa v14, v16, v13 dst_sel:DWORD dst_unused:UNUSED_PAD src0_sel:DWORD src1_sel:WORD_1
	v_or_b32_sdwa v17, v34, v17 dst_sel:DWORD dst_unused:UNUSED_PAD src0_sel:DWORD src1_sel:WORD_1
	v_or_b32_sdwa v16, v36, v32 dst_sel:DWORD dst_unused:UNUSED_PAD src0_sel:DWORD src1_sel:WORD_1
	v_cvt_pk_bf16_f32 v13, 0, v37
	global_store_dwordx4 v[50:51], v[14:17], off
	v_cvt_pk_bf16_f32 v9, 0, v35
	v_and_b32_e32 v13, 0xffff0000, v13
	v_cvt_pk_bf16_f32 v14, 0, v33
	v_or_b32_sdwa v15, v13, v9 dst_sel:DWORD dst_unused:UNUSED_PAD src0_sel:DWORD src1_sel:WORD_1
	v_cvt_pk_bf16_f32 v16, 0, v45
	v_cvt_pk_bf16_f32 v17, 0, v41
	v_and_b32_e32 v14, 0xffff0000, v14
	v_cvt_pk_bf16_f32 v13, 0, v39
	v_cvt_pk_bf16_f32 v9, 0, v43
	v_and_b32_e32 v16, 0xffff0000, v16
	v_and_b32_e32 v32, 0xffff0000, v17
	v_or_b32_sdwa v14, v14, v38 dst_sel:DWORD dst_unused:UNUSED_PAD src0_sel:DWORD src1_sel:WORD_1
	v_or_b32_sdwa v17, v16, v9 dst_sel:DWORD dst_unused:UNUSED_PAD src0_sel:DWORD src1_sel:WORD_1
	v_or_b32_sdwa v16, v32, v13 dst_sel:DWORD dst_unused:UNUSED_PAD src0_sel:DWORD src1_sel:WORD_1
	global_store_dwordx4 v[48:49], v[14:17], off
	s_branch .LBB0_363

; template <int WM, int WN>
; __device__ __forceinline__ void store_tile_bf16(const f32x4 (&acc)[WM][WN], u16* dst, int ld, char* smem) {
;   constexpr int BM = 32 * WM, BN = 32 * WN, STR = BN + 8;
;   const int tid = opaque_tid(), lane = tid & 63, wid = tid >> 6;
;   const int wr = wid >> 1, wc = wid & 1, fr = lane & 15, fq = lane >> 4;
;   u16* T = reinterpret_cast<u16*>(smem);
; #pragma unroll
;   for (int m = 0; m < WM; ++m)
; #pragma unroll
;     for (int n = 0; n < WN; ++n)
; #pragma unroll
;       for (int j = 0; j < 4; ++j)
;         T[(wr * 16 * WM + m * 16 + fq * 4 + j) * STR + wc * 16 * WN + n * 16 + fr] = f2bf(acc[m][n][j]);
;   __syncthreads();
.LBB0_423:
	v_mov_b32_e32 v64, v232
	v_lshrrev_b32_e32 v66, 2, v64
	s_waitcnt lgkmcnt(0)
	v_lshrrev_b32_e32 v65, 1, v64
	v_and_b32_e32 v66, 12, v66
	v_and_or_b32 v65, v65, s51, v66
	v_and_b32_e32 v66, 0x4f, v64
	v_mul_lo_u32 v65, v65, s53
	v_cvt_pk_bf16_f32 v44, 0, v44
	v_lshl_add_u32 v65, v66, 1, v65
	ds_write_b16_d16_hi v65, v44
	v_cvt_pk_bf16_f32 v44, 0, v45
	ds_write_b16_d16_hi v65, v44 offset:272
	v_cvt_pk_bf16_f32 v44, 0, v46
	ds_write_b16_d16_hi v65, v44 offset:544
	v_cvt_pk_bf16_f32 v44, 0, v47
	ds_write_b16_d16_hi v65, v44 offset:816
	v_cvt_pk_bf16_f32 v40, 0, v40
	ds_write_b16_d16_hi v65, v40 offset:32
	v_cvt_pk_bf16_f32 v40, 0, v41
	ds_write_b16_d16_hi v65, v40 offset:304
	v_cvt_pk_bf16_f32 v40, 0, v42
	ds_write_b16_d16_hi v65, v40 offset:576
	v_cvt_pk_bf16_f32 v40, 0, v43
	ds_write_b16_d16_hi v65, v40 offset:848
	v_cvt_pk_bf16_f32 v36, 0, v36
	ds_write_b16_d16_hi v65, v36 offset:64
	v_cvt_pk_bf16_f32 v36, 0, v37
	ds_write_b16_d16_hi v65, v36 offset:336
	v_cvt_pk_bf16_f32 v36, 0, v38
	ds_write_b16_d16_hi v65, v36 offset:608
	v_cvt_pk_bf16_f32 v36, 0, v39
	ds_write_b16_d16_hi v65, v36 offset:880
	v_cvt_pk_bf16_f32 v32, 0, v32
	ds_write_b16_d16_hi v65, v32 offset:96
	v_cvt_pk_bf16_f32 v32, 0, v33
	ds_write_b16_d16_hi v65, v32 offset:368
	v_cvt_pk_bf16_f32 v32, 0, v34
	ds_write_b16_d16_hi v65, v32 offset:640
	v_cvt_pk_bf16_f32 v32, 0, v35
	ds_write_b16_d16_hi v65, v32 offset:912
	v_cvt_pk_bf16_f32 v28, 0, v28
	ds_write_b16_d16_hi v65, v28 offset:4352
	v_cvt_pk_bf16_f32 v28, 0, v29
	ds_write_b16_d16_hi v65, v28 offset:4624
	v_cvt_pk_bf16_f32 v28, 0, v30
	ds_write_b16_d16_hi v65, v28 offset:4896
	v_cvt_pk_bf16_f32 v28, 0, v31
	ds_write_b16_d16_hi v65, v28 offset:5168
	v_cvt_pk_bf16_f32 v24, 0, v24
	ds_write_b16_d16_hi v65, v24 offset:4384
	v_cvt_pk_bf16_f32 v24, 0, v25
	ds_write_b16_d16_hi v65, v24 offset:4656
	v_cvt_pk_bf16_f32 v24, 0, v26
	ds_write_b16_d16_hi v65, v24 offset:4928
	v_cvt_pk_bf16_f32 v24, 0, v27
	ds_write_b16_d16_hi v65, v24 offset:5200
	v_cvt_pk_bf16_f32 v20, 0, v20
	ds_write_b16_d16_hi v65, v20 offset:4416
	v_cvt_pk_bf16_f32 v20, 0, v21
	ds_write_b16_d16_hi v65, v20 offset:4688
	v_cvt_pk_bf16_f32 v20, 0, v22
	ds_write_b16_d16_hi v65, v20 offset:4960
	v_cvt_pk_bf16_f32 v20, 0, v23
	ds_write_b16_d16_hi v65, v20 offset:5232
	v_cvt_pk_bf16_f32 v16, 0, v16
	ds_write_b16_d16_hi v65, v16 offset:4448
	v_cvt_pk_bf16_f32 v16, 0, v17
	ds_write_b16_d16_hi v65, v16 offset:4720
	v_cvt_pk_bf16_f32 v16, 0, v18
	ds_write_b16_d16_hi v65, v16 offset:4992
	v_cvt_pk_bf16_f32 v16, 0, v19
	ds_write_b16_d16_hi v65, v16 offset:5264
	v_cvt_pk_bf16_f32 v12, 0, v12
	ds_write_b16_d16_hi v65, v12 offset:8704
	v_cvt_pk_bf16_f32 v12, 0, v13
	ds_write_b16_d16_hi v65, v12 offset:8976
	v_cvt_pk_bf16_f32 v12, 0, v14
	ds_write_b16_d16_hi v65, v12 offset:9248
	v_cvt_pk_bf16_f32 v12, 0, v15
	ds_write_b16_d16_hi v65, v12 offset:9520
	v_cvt_pk_bf16_f32 v8, 0, v8
	ds_write_b16_d16_hi v65, v8 offset:8736
	v_cvt_pk_bf16_f32 v8, 0, v9
	ds_write_b16_d16_hi v65, v8 offset:9008
	v_cvt_pk_bf16_f32 v8, 0, v10
	ds_write_b16_d16_hi v65, v8 offset:9280
	v_cvt_pk_bf16_f32 v8, 0, v11
	ds_write_b16_d16_hi v65, v8 offset:9552
	v_cvt_pk_bf16_f32 v4, 0, v4
	ds_write_b16_d16_hi v65, v4 offset:8768
	v_cvt_pk_bf16_f32 v4, 0, v5
	ds_write_b16_d16_hi v65, v4 offset:9040
	v_cvt_pk_bf16_f32 v4, 0, v6
	ds_write_b16_d16_hi v65, v4 offset:9312
	v_cvt_pk_bf16_f32 v4, 0, v7
	ds_write_b16_d16_hi v65, v4 offset:9584
	v_cvt_pk_bf16_f32 v0, 0, v0
	ds_write_b16_d16_hi v65, v0 offset:8800
	v_cvt_pk_bf16_f32 v0, 0, v1
	ds_write_b16_d16_hi v65, v0 offset:9072
	v_cvt_pk_bf16_f32 v0, 0, v2
	ds_write_b16_d16_hi v65, v0 offset:9344
	v_cvt_pk_bf16_f32 v0, 0, v3
	ds_write_b16_d16_hi v65, v0 offset:9616
	v_cvt_pk_bf16_f32 v0, 0, v60
	ds_write_b16_d16_hi v65, v0 offset:13056
	v_cvt_pk_bf16_f32 v0, 0, v61
	ds_write_b16_d16_hi v65, v0 offset:13328
	v_cvt_pk_bf16_f32 v0, 0, v62
	ds_write_b16_d16_hi v65, v0 offset:13600
	v_cvt_pk_bf16_f32 v0, 0, v63
	ds_write_b16_d16_hi v65, v0 offset:13872
	v_cvt_pk_bf16_f32 v0, 0, v56
	ds_write_b16_d16_hi v65, v0 offset:13088
	v_cvt_pk_bf16_f32 v0, 0, v57
	ds_write_b16_d16_hi v65, v0 offset:13360
	v_cvt_pk_bf16_f32 v0, 0, v58
	ds_write_b16_d16_hi v65, v0 offset:13632
	v_cvt_pk_bf16_f32 v0, 0, v59
	ds_write_b16_d16_hi v65, v0 offset:13904
	v_cvt_pk_bf16_f32 v0, 0, v52
	ds_write_b16_d16_hi v65, v0 offset:13120
	v_cvt_pk_bf16_f32 v0, 0, v53
	ds_write_b16_d16_hi v65, v0 offset:13392
	v_cvt_pk_bf16_f32 v0, 0, v54
	ds_write_b16_d16_hi v65, v0 offset:13664
	v_cvt_pk_bf16_f32 v0, 0, v55
	ds_write_b16_d16_hi v65, v0 offset:13936
	v_cvt_pk_bf16_f32 v0, 0, v48
	ds_write_b16_d16_hi v65, v0 offset:13152
	v_cvt_pk_bf16_f32 v0, 0, v49
	ds_write_b16_d16_hi v65, v0 offset:13424
	v_cvt_pk_bf16_f32 v0, 0, v50
	ds_write_b16_d16_hi v65, v0 offset:13696
	s_lshl_b32 s22, s22, 7
	s_mul_hi_i32 s14, s16, 0x130000
	s_mul_i32 s16, s16, 0x130000
	v_cvt_pk_bf16_f32 v0, 0, v51
	s_add_u32 s24, s40, s16
	ds_write_b16_d16_hi v65, v0 offset:13968
	v_ashrrev_i32_e32 v0, 31, v64
	s_addc_u32 s14, s41, s14
	s_ashr_i32 s23, s22, 31
	v_lshrrev_b32_e32 v0, 28, v0
	s_lshl_b64 s[16:17], s[22:23], 1
	v_add_u32_e32 v0, v64, v0
	s_add_u32 s16, s24, s16
	v_ashrrev_i32_e32 v6, 4, v0
	v_and_b32_e32 v0, -16, v0
	s_addc_u32 s17, s14, s17
	v_sub_u32_e32 v0, v64, v0
	v_lshlrev_b32_e32 v4, 3, v0
	v_mov_b64_e32 v[8:9], s[16:17]
	v_mul_lo_u32 v1, v6, s53
	v_ashrrev_i32_e32 v5, 31, v4
	v_mad_i64_i32 v[6:7], s[16:17], v6, s54, v[8:9]
	v_lshl_add_u64 v[10:11], v[4:5], 1, v[6:7]
	v_add_u32_e32 v4, 0x100, v64
	v_ashrrev_i32_e32 v5, 31, v4
	v_lshrrev_b32_e32 v5, 28, v5
	v_lshl_add_u32 v0, v0, 4, v1
	v_add_u32_e32 v5, v4, v5
	s_waitcnt lgkmcnt(0)
	s_barrier
; template <int WM, int WN>
; __device__ __forceinline__ void store_tile_bf16(const f32x4 (&acc)[WM][WN], u16* dst, int ld, char* smem) {
;     ...
;   constexpr int CPR = BN / 8;
; #pragma unroll
;   for (int i = 0; i < BM * CPR / 256; ++i) {
;     int q = tid + 256 * i, row = q / CPR, c = q % CPR;
;     uint4 v = *reinterpret_cast<const uint4*>(T + row * STR + c * 8);
;     *reinterpret_cast<uint4*>(dst + (size_t)row * ld + c * 8) = v;
;   }
	ds_read_b128 v[0:3], v0
	v_ashrrev_i32_e32 v12, 4, v5
	v_and_b32_e32 v5, -16, v5
	v_sub_u32_e32 v13, v4, v5
	v_mul_lo_u32 v4, v12, s53
	v_lshl_add_u32 v4, v13, 4, v4
	ds_read_b128 v[4:7], v4
	s_waitcnt lgkmcnt(1)
	global_store_dwordx4 v[10:11], v[0:3], off
	s_add_i32 s55, s55, s61
	s_cmp_lt_i32 s55, s47
	v_lshlrev_b32_e32 v0, 3, v13
	v_ashrrev_i32_e32 v1, 31, v0
	v_mad_i64_i32 v[2:3], s[16:17], v12, s54, v[8:9]
	v_lshl_add_u64 v[0:1], v[0:1], 1, v[2:3]
	s_waitcnt lgkmcnt(0)
	global_store_dwordx4 v[0:1], v[4:7], off
	v_add_u32_e32 v0, 0x200, v64
	v_ashrrev_i32_e32 v1, 31, v0
	v_lshrrev_b32_e32 v1, 28, v1
	v_add_u32_e32 v1, v0, v1
	v_ashrrev_i32_e32 v6, 4, v1
	v_and_b32_e32 v1, -16, v1
	v_sub_u32_e32 v0, v0, v1
	v_lshlrev_b32_e32 v4, 3, v0
	v_mul_lo_u32 v1, v6, s53
	v_ashrrev_i32_e32 v5, 31, v4
	v_mad_i64_i32 v[6:7], s[16:17], v6, s54, v[8:9]
	v_lshl_add_u64 v[10:11], v[4:5], 1, v[6:7]
	v_add_u32_e32 v4, 0x300, v64
	v_ashrrev_i32_e32 v5, 31, v4
	v_lshrrev_b32_e32 v5, 28, v5
	v_lshl_add_u32 v0, v0, 4, v1
	v_add_u32_e32 v5, v4, v5
	ds_read_b128 v[0:3], v0
	v_ashrrev_i32_e32 v12, 4, v5
	v_and_b32_e32 v5, -16, v5
	v_sub_u32_e32 v13, v4, v5
	v_mul_lo_u32 v4, v12, s53
	v_lshl_add_u32 v4, v13, 4, v4
	ds_read_b128 v[4:7], v4
	s_waitcnt lgkmcnt(1)
	global_store_dwordx4 v[10:11], v[0:3], off
	s_nop 1
	v_lshlrev_b32_e32 v0, 3, v13
	v_ashrrev_i32_e32 v1, 31, v0
	v_mad_i64_i32 v[2:3], s[16:17], v12, s54, v[8:9]
	v_lshl_add_u64 v[0:1], v[0:1], 1, v[2:3]
	s_waitcnt lgkmcnt(0)
	global_store_dwordx4 v[0:1], v[4:7], off
	v_add_u32_e32 v0, 0x400, v64
	v_ashrrev_i32_e32 v1, 31, v0
	v_lshrrev_b32_e32 v1, 28, v1
	v_add_u32_e32 v1, v0, v1
	v_ashrrev_i32_e32 v6, 4, v1
	v_and_b32_e32 v1, -16, v1
	v_sub_u32_e32 v0, v0, v1
	v_lshlrev_b32_e32 v4, 3, v0
	v_mul_lo_u32 v1, v6, s53
	v_ashrrev_i32_e32 v5, 31, v4
	v_mad_i64_i32 v[6:7], s[16:17], v6, s54, v[8:9]
	v_lshl_add_u64 v[10:11], v[4:5], 1, v[6:7]
	v_add_u32_e32 v4, 0x500, v64
	v_ashrrev_i32_e32 v5, 31, v4
	v_lshrrev_b32_e32 v5, 28, v5
	v_lshl_add_u32 v0, v0, 4, v1
	v_add_u32_e32 v5, v4, v5
	ds_read_b128 v[0:3], v0
	v_ashrrev_i32_e32 v12, 4, v5
	v_and_b32_e32 v5, -16, v5
	v_sub_u32_e32 v13, v4, v5
	v_mul_lo_u32 v4, v12, s53
	v_lshl_add_u32 v4, v13, 4, v4
	ds_read_b128 v[4:7], v4
	s_waitcnt lgkmcnt(1)
	global_store_dwordx4 v[10:11], v[0:3], off
	s_nop 1
	v_lshlrev_b32_e32 v0, 3, v13
	v_ashrrev_i32_e32 v1, 31, v0
	v_mad_i64_i32 v[2:3], s[16:17], v12, s54, v[8:9]
	v_lshl_add_u64 v[0:1], v[0:1], 1, v[2:3]
	s_waitcnt lgkmcnt(0)
	global_store_dwordx4 v[0:1], v[4:7], off
	v_add_u32_e32 v0, 0x600, v64
	v_ashrrev_i32_e32 v1, 31, v0
	v_lshrrev_b32_e32 v1, 28, v1
	v_add_u32_e32 v1, v0, v1
	v_ashrrev_i32_e32 v6, 4, v1
	v_and_b32_e32 v1, -16, v1
	v_sub_u32_e32 v0, v0, v1
	v_lshlrev_b32_e32 v4, 3, v0
	v_mul_lo_u32 v1, v6, s53
	v_ashrrev_i32_e32 v5, 31, v4
	v_mad_i64_i32 v[6:7], s[16:17], v6, s54, v[8:9]
	v_lshl_add_u64 v[10:11], v[4:5], 1, v[6:7]
	v_add_u32_e32 v4, 0x700, v64
	v_ashrrev_i32_e32 v5, 31, v4
	v_lshrrev_b32_e32 v5, 28, v5
	v_lshl_add_u32 v0, v0, 4, v1
	v_add_u32_e32 v5, v4, v5
	ds_read_b128 v[0:3], v0
	v_ashrrev_i32_e32 v12, 4, v5
	v_and_b32_e32 v5, -16, v5
	v_sub_u32_e32 v13, v4, v5
	v_mul_lo_u32 v4, v12, s53
	v_lshl_add_u32 v4, v13, 4, v4
	ds_read_b128 v[4:7], v4
	s_waitcnt lgkmcnt(1)
	global_store_dwordx4 v[10:11], v[0:3], off
	s_nop 1
	v_lshlrev_b32_e32 v0, 3, v13
	v_ashrrev_i32_e32 v1, 31, v0
	v_mad_i64_i32 v[2:3], s[16:17], v12, s54, v[8:9]
	v_lshl_add_u64 v[0:1], v[0:1], 1, v[2:3]
	s_waitcnt lgkmcnt(0)
	global_store_dwordx4 v[0:1], v[4:7], off
	s_cbranch_scc0 .LBB0_431

; __device__ void phase_inproj(const Params& p, int layer, char* smem) {
;     ...
;     if (cb >= 26 && cb <= 29) {
;       float mx = 0.f;
; #pragma unroll
;       for (int m = 0; m < 4; ++m)
; #pragma unroll
;         for (int j = 0; j < 4; ++j) {
;           float ss = 0.f;
; #pragma unroll
;           for (int n = 0; n < 4; ++n) ss += acc[m][n][j] * acc[m][n][j];
;           ss += __shfl_xor(ss, 1);
;           ss += __shfl_xor(ss, 2);
;           ss += __shfl_xor(ss, 4);
;           ss += __shfl_xor(ss, 8);
;           mx = fmaxf(mx, ss);
;         }
.LBB0_428:
	s_sub_i32 s14, s22, 26
	s_cmp_gt_u32 s14, 3
	s_cbranch_scc1 .LBB0_423
	v_and_b32_e32 v65, 64, v129
	v_xor_b32_e32 v64, 1, v129
	v_add_u32_e32 v65, 64, v65
	v_mul_f32_e32 v66, v44, v44
	v_mul_f32_e32 v71, v45, v45
	v_cmp_lt_i32_e32 vcc, v64, v65
	v_fmac_f32_e32 v66, v40, v40
	v_fmac_f32_e32 v71, v41, v41
	v_mul_f32_e32 v73, v46, v46
	v_mul_f32_e32 v75, v47, v47
	v_cndmask_b32_e32 v64, v129, v64, vcc
	v_fmac_f32_e32 v66, v36, v36
	v_fmac_f32_e32 v71, v37, v37
	v_fmac_f32_e32 v73, v42, v42
	v_fmac_f32_e32 v75, v43, v43
	v_lshlrev_b32_e32 v64, 2, v64
	v_fmac_f32_e32 v66, v32, v32
	v_fmac_f32_e32 v71, v33, v33
	v_fmac_f32_e32 v73, v38, v38
	v_fmac_f32_e32 v75, v39, v39
	ds_bpermute_b32 v67, v64, v66
	ds_bpermute_b32 v72, v64, v71
	v_fmac_f32_e32 v73, v34, v34
	v_fmac_f32_e32 v75, v35, v35
	ds_bpermute_b32 v74, v64, v73
	ds_bpermute_b32 v76, v64, v75
	v_xor_b32_e32 v68, 2, v129
	v_cmp_lt_i32_e32 vcc, v68, v65
	s_waitcnt lgkmcnt(3)
	v_add_f32_e32 v66, v66, v67
	s_waitcnt lgkmcnt(2)
	v_add_f32_e32 v71, v71, v72
	v_cndmask_b32_e32 v68, v129, v68, vcc
	v_lshlrev_b32_e32 v68, 2, v68
	ds_bpermute_b32 v67, v68, v66
	ds_bpermute_b32 v72, v68, v71
	s_waitcnt lgkmcnt(3)
	v_add_f32_e32 v73, v73, v74
	s_waitcnt lgkmcnt(2)
	v_add_f32_e32 v75, v75, v76
	ds_bpermute_b32 v74, v68, v73
	ds_bpermute_b32 v76, v68, v75
	v_xor_b32_e32 v69, 4, v129
	v_cmp_lt_i32_e32 vcc, v69, v65
	s_waitcnt lgkmcnt(3)
	v_add_f32_e32 v66, v66, v67
	s_waitcnt lgkmcnt(2)
	v_add_f32_e32 v71, v71, v72
	v_cndmask_b32_e32 v69, v129, v69, vcc
	v_lshlrev_b32_e32 v69, 2, v69
	ds_bpermute_b32 v67, v69, v66
	ds_bpermute_b32 v72, v69, v71
	s_waitcnt lgkmcnt(3)
	v_add_f32_e32 v73, v73, v74
	s_waitcnt lgkmcnt(2)
	v_add_f32_e32 v75, v75, v76
	ds_bpermute_b32 v74, v69, v73
	ds_bpermute_b32 v76, v69, v75
	v_xor_b32_e32 v70, 8, v129
	v_cmp_lt_i32_e32 vcc, v70, v65
	s_waitcnt lgkmcnt(3)
	v_add_f32_e32 v66, v66, v67
	s_waitcnt lgkmcnt(2)
	v_add_f32_e32 v71, v71, v72
	v_cndmask_b32_e32 v70, v129, v70, vcc
	v_lshlrev_b32_e32 v70, 2, v70
	ds_bpermute_b32 v67, v70, v66
	ds_bpermute_b32 v72, v70, v71
	s_waitcnt lgkmcnt(3)
	v_add_f32_e32 v73, v73, v74
	s_waitcnt lgkmcnt(2)
	v_add_f32_e32 v75, v75, v76
	ds_bpermute_b32 v74, v70, v73
	ds_bpermute_b32 v76, v70, v75
	s_waitcnt lgkmcnt(3)
	v_add_f32_e32 v66, v66, v67
	s_waitcnt lgkmcnt(2)
	v_add_f32_e32 v67, v71, v72
	v_max3_f32 v66, v66, 0, v67
	s_waitcnt lgkmcnt(1)
	v_add_f32_e32 v67, v73, v74
	s_waitcnt lgkmcnt(0)
	v_add_f32_e32 v71, v75, v76
	v_max3_f32 v66, v66, v67, v71
	v_mul_f32_e32 v67, v28, v28
	v_mul_f32_e32 v72, v29, v29
	v_fmac_f32_e32 v67, v24, v24
	v_fmac_f32_e32 v72, v25, v25
	v_mul_f32_e32 v74, v30, v30
	v_fmac_f32_e32 v67, v20, v20
	v_fmac_f32_e32 v72, v21, v21
	v_fmac_f32_e32 v74, v26, v26
	v_fmac_f32_e32 v67, v16, v16
	v_fmac_f32_e32 v72, v17, v17
	v_fmac_f32_e32 v74, v22, v22
	ds_bpermute_b32 v71, v64, v67
	ds_bpermute_b32 v73, v64, v72
	v_fmac_f32_e32 v74, v18, v18
	ds_bpermute_b32 v75, v64, v74
	v_mul_f32_e32 v76, v31, v31
	s_waitcnt lgkmcnt(2)
	v_add_f32_e32 v67, v67, v71
	s_waitcnt lgkmcnt(1)
	v_add_f32_e32 v72, v72, v73
	ds_bpermute_b32 v71, v68, v67
	ds_bpermute_b32 v73, v68, v72
	s_waitcnt lgkmcnt(2)
	v_add_f32_e32 v74, v74, v75
	ds_bpermute_b32 v75, v68, v74
	v_fmac_f32_e32 v76, v27, v27
	s_waitcnt lgkmcnt(2)
	v_add_f32_e32 v67, v67, v71
	s_waitcnt lgkmcnt(1)
	v_add_f32_e32 v72, v72, v73
	ds_bpermute_b32 v71, v69, v67
	ds_bpermute_b32 v73, v69, v72
	s_waitcnt lgkmcnt(2)
	v_add_f32_e32 v74, v74, v75
	ds_bpermute_b32 v75, v69, v74
	v_fmac_f32_e32 v76, v23, v23
	s_waitcnt lgkmcnt(2)
	v_add_f32_e32 v67, v67, v71
	s_waitcnt lgkmcnt(1)
	v_add_f32_e32 v72, v72, v73
	ds_bpermute_b32 v71, v70, v67
	ds_bpermute_b32 v73, v70, v72
	s_waitcnt lgkmcnt(2)
	v_add_f32_e32 v74, v74, v75
	ds_bpermute_b32 v75, v70, v74
	v_fmac_f32_e32 v76, v19, v19
	ds_bpermute_b32 v77, v64, v76
	s_waitcnt lgkmcnt(3)
	v_add_f32_e32 v67, v67, v71
	s_waitcnt lgkmcnt(2)
	v_add_f32_e32 v71, v72, v73
	v_max3_f32 v66, v66, v67, v71
	s_waitcnt lgkmcnt(1)
	v_add_f32_e32 v67, v74, v75
	v_mul_f32_e32 v73, v12, v12
	v_mul_f32_e32 v75, v13, v13
	v_fmac_f32_e32 v73, v8, v8
	v_fmac_f32_e32 v75, v9, v9
	s_waitcnt lgkmcnt(0)
	v_add_f32_e32 v71, v76, v77
	v_fmac_f32_e32 v73, v4, v4
	v_fmac_f32_e32 v75, v5, v5
	ds_bpermute_b32 v72, v68, v71
	v_fmac_f32_e32 v73, v0, v0
	v_fmac_f32_e32 v75, v1, v1
	ds_bpermute_b32 v74, v64, v73
	ds_bpermute_b32 v76, v64, v75
	s_waitcnt lgkmcnt(2)
	v_add_f32_e32 v71, v71, v72
	ds_bpermute_b32 v72, v69, v71
	s_waitcnt lgkmcnt(2)
	v_add_f32_e32 v73, v73, v74
	s_waitcnt lgkmcnt(1)
; __device__ void phase_inproj(const Params& p, int layer, char* smem) {
;     ...
;           float ss = 0.f;
; #pragma unroll
;           for (int n = 0; n < 4; ++n) ss += acc[m][n][j] * acc[m][n][j];
;           ss += __shfl_xor(ss, 1);
;           ss += __shfl_xor(ss, 2);
;           ss += __shfl_xor(ss, 4);
;           ss += __shfl_xor(ss, 8);
;           mx = fmaxf(mx, ss);
;         }
;       mx = fmaxf(mx, __shfl_xor(mx, 16));
;       mx = fmaxf(mx, __shfl_xor(mx, 32));
;       if (lane == 0) {
;         unsigned* km = reinterpret_cast<unsigned*>(wsb(p) + OFF_MISC) + 64 + layer * 16 + (rb >> 7) * 8 + (cb - 26) * 2 + wc;
;         atomicMax(km, __float_as_uint(mx));
;       }
	v_add_f32_e32 v75, v75, v76
	ds_bpermute_b32 v74, v68, v73
	ds_bpermute_b32 v76, v68, v75
	s_waitcnt lgkmcnt(2)
	v_add_f32_e32 v71, v71, v72
	ds_bpermute_b32 v72, v70, v71
	s_waitcnt lgkmcnt(2)
	v_add_f32_e32 v73, v73, v74
	s_waitcnt lgkmcnt(1)
	v_add_f32_e32 v75, v75, v76
	ds_bpermute_b32 v74, v69, v73
	ds_bpermute_b32 v76, v69, v75
	s_waitcnt lgkmcnt(2)
	v_add_f32_e32 v71, v71, v72
	v_max3_f32 v66, v66, v67, v71
	s_waitcnt lgkmcnt(1)
	v_add_f32_e32 v67, v73, v74
	s_waitcnt lgkmcnt(0)
	v_add_f32_e32 v72, v75, v76
	v_mul_f32_e32 v74, v14, v14
	v_mul_f32_e32 v76, v15, v15
	v_fmac_f32_e32 v74, v10, v10
	v_fmac_f32_e32 v76, v11, v11
	v_fmac_f32_e32 v74, v6, v6
	v_fmac_f32_e32 v76, v7, v7
	v_fmac_f32_e32 v74, v2, v2
	v_fmac_f32_e32 v76, v3, v3
	ds_bpermute_b32 v71, v70, v67
	ds_bpermute_b32 v73, v70, v72
	ds_bpermute_b32 v75, v64, v74
	ds_bpermute_b32 v77, v64, v76
	s_waitcnt lgkmcnt(3)
	v_add_f32_e32 v67, v67, v71
	s_waitcnt lgkmcnt(2)
	v_add_f32_e32 v71, v72, v73
	s_waitcnt lgkmcnt(1)
	v_add_f32_e32 v72, v74, v75
	s_waitcnt lgkmcnt(0)
	v_add_f32_e32 v74, v76, v77
	v_mul_f32_e32 v76, v60, v60
	v_fmac_f32_e32 v76, v56, v56
	v_fmac_f32_e32 v76, v52, v52
	ds_bpermute_b32 v73, v68, v72
	ds_bpermute_b32 v75, v68, v74
	v_fmac_f32_e32 v76, v48, v48
	ds_bpermute_b32 v77, v64, v76
	v_max3_f32 v66, v66, v67, v71
	s_waitcnt lgkmcnt(2)
	v_add_f32_e32 v72, v72, v73
	s_waitcnt lgkmcnt(1)
	v_add_f32_e32 v74, v74, v75
	ds_bpermute_b32 v73, v69, v72
	ds_bpermute_b32 v75, v69, v74
	s_waitcnt lgkmcnt(2)
	v_add_f32_e32 v76, v76, v77
	ds_bpermute_b32 v77, v68, v76
	s_waitcnt lgkmcnt(2)
	v_add_f32_e32 v72, v72, v73
	s_waitcnt lgkmcnt(1)
	v_add_f32_e32 v74, v74, v75
	ds_bpermute_b32 v73, v70, v72
	ds_bpermute_b32 v75, v70, v74
	s_waitcnt lgkmcnt(2)
	v_add_f32_e32 v76, v76, v77
	ds_bpermute_b32 v77, v69, v76
	s_waitcnt lgkmcnt(2)
	v_add_f32_e32 v67, v72, v73
	s_waitcnt lgkmcnt(1)
	v_add_f32_e32 v71, v74, v75
	v_mul_f32_e32 v72, v61, v61
	v_max3_f32 v66, v66, v67, v71
	s_waitcnt lgkmcnt(0)
	v_add_f32_e32 v67, v76, v77
	v_fmac_f32_e32 v72, v57, v57
	v_mul_f32_e32 v74, v62, v62
	v_mul_f32_e32 v76, v63, v63
	v_fmac_f32_e32 v72, v53, v53
	v_fmac_f32_e32 v74, v58, v58
	v_fmac_f32_e32 v76, v59, v59
	v_fmac_f32_e32 v72, v49, v49
	v_fmac_f32_e32 v74, v54, v54
	v_fmac_f32_e32 v76, v55, v55
	ds_bpermute_b32 v73, v64, v72
	v_fmac_f32_e32 v74, v50, v50
	v_fmac_f32_e32 v76, v51, v51
	ds_bpermute_b32 v75, v64, v74
	ds_bpermute_b32 v64, v64, v76
	s_waitcnt lgkmcnt(2)
	v_add_f32_e32 v72, v72, v73
	ds_bpermute_b32 v73, v68, v72
	ds_bpermute_b32 v71, v70, v67
	s_waitcnt lgkmcnt(3)
	v_add_f32_e32 v74, v74, v75
	s_waitcnt lgkmcnt(2)
	v_add_f32_e32 v64, v76, v64
	ds_bpermute_b32 v75, v68, v74
	ds_bpermute_b32 v68, v68, v64
	s_waitcnt lgkmcnt(3)
	v_add_f32_e32 v72, v72, v73
	ds_bpermute_b32 v73, v69, v72
	s_waitcnt lgkmcnt(3)
	v_add_f32_e32 v67, v67, v71
	s_waitcnt lgkmcnt(2)
	v_add_f32_e32 v74, v74, v75
	s_waitcnt lgkmcnt(1)
	v_add_f32_e32 v64, v64, v68
	ds_bpermute_b32 v75, v69, v74
	ds_bpermute_b32 v68, v69, v64
	s_waitcnt lgkmcnt(2)
	v_add_f32_e32 v69, v72, v73
	ds_bpermute_b32 v72, v70, v69
	s_waitcnt lgkmcnt(2)
	v_add_f32_e32 v73, v74, v75
	s_waitcnt lgkmcnt(1)
	v_add_f32_e32 v64, v64, v68
	ds_bpermute_b32 v74, v70, v73
	ds_bpermute_b32 v68, v70, v64
	s_waitcnt lgkmcnt(2)
	v_add_f32_e32 v69, v69, v72
	v_max3_f32 v66, v66, v67, v69
	s_waitcnt lgkmcnt(1)
	v_add_f32_e32 v67, v73, v74
	s_waitcnt lgkmcnt(0)
	v_add_f32_e32 v64, v64, v68
	v_max3_f32 v64, v66, v67, v64
	v_xor_b32_e32 v66, 16, v129
	v_cmp_lt_i32_e32 vcc, v66, v65
	s_nop 1
	v_cndmask_b32_e32 v66, v129, v66, vcc
	v_lshlrev_b32_e32 v66, 2, v66
	ds_bpermute_b32 v66, v66, v64
	s_waitcnt lgkmcnt(0)
	v_max_f32_e32 v64, v64, v66
	v_xor_b32_e32 v66, 32, v129
	v_cmp_lt_i32_e32 vcc, v66, v65
	s_nop 1
	v_cndmask_b32_e32 v65, v129, v66, vcc
	v_lshlrev_b32_e32 v65, 2, v65
	ds_bpermute_b32 v65, v65, v64
	s_and_saveexec_b64 s[24:25], s[10:11]
	s_cbranch_execz .LBB0_422
	s_waitcnt lgkmcnt(0)
	v_max_f32_e32 v66, v64, v65
	v_mov_b32_e32 v64, v117
	v_mov_b32_e32 v119, v117
	v_readfirstlane_b32 s14, v64
	s_ashr_i32 s17, s14, 31
	s_add_u32 s14, s28, s14
	s_addc_u32 s17, s29, s17
	s_ashr_i32 s23, s16, 4
	s_and_b32 s26, s23, -8
	s_ashr_i32 s27, s26, 31
	s_lshl_b64 s[26:27], s[26:27], 2
	s_add_u32 s23, s14, s26
	s_addc_u32 s17, s17, s27
	s_lshl_b32 s14, s22, 1
	s_lshl_b64 s[26:27], s[14:15], 2
	s_add_u32 s26, s23, s26
	s_addc_u32 s27, s17, s27
	v_lshl_add_u64 v[64:65], s[26:27], 0, v[118:119]
	v_add_co_u32_e32 v64, vcc, 0x1e8a4000, v64
	s_nop 1
	v_addc_co_u32_e32 v65, vcc, 0, v65, vcc
	global_atomic_umax v[64:65], v66, off offset:2160
	s_branch .LBB0_422

; template <int DH, int MODE>
; __device__ void attn_item(const Params& p, int layer, int b, int blk, int head, char* smem) {
;     ...
;   {
;     constexpr int OST = DH + 4;
;     constexpr int CPR = DH / 8;
;     constexpr int NCH = 128 * CPR / 256;
;     float* Of = reinterpret_cast<float*>(smem);
;     uint4 gt[NCH];
; #pragma unroll
;     for (int i = 0; i < NCH; ++i) {
;       int q = tid + 256 * i, r = q / CPR, c = (q % CPR) * 8;
;       gt[i] = *reinterpret_cast<const uint4*>(P + (tq0 + r) * NP + gcol + c);
;     }
;     float lis[2][4];
; #pragma unroll
;     for (int m = 0; m < 2; ++m)
; #pragma unroll
;       for (int j = 0; j < 4; ++j) lis[m][j] = (MODE == 0) ? linv_s[wid * 32 + m * 16 + fq * 4 + j] : 1.f;
;     if (MODE == 0) __syncthreads();
; #pragma unroll
;     for (int m = 0; m < 2; ++m)
; #pragma unroll
;       for (int j = 0; j < 4; ++j) {
;         int r = wid * 32 + m * 16 + fq * 4 + j;
; #pragma unroll
;         for (int n = 0; n < NDT; ++n) Of[r * OST + n * 16 + fr] = o[m][n][j] * lis[m][j];
;       }
.LBB0_470:
	s_ashr_i32 s13, s86, 31
	s_add_u32 s12, s28, s86
	s_addc_u32 s13, s29, s13
	s_lshl_b32 s14, s83, 1
	s_add_u32 s16, s50, s14
	s_addc_u32 s17, s51, 0
	v_lshl_add_u64 v[2:3], s[20:21], 0, v[134:135]
	v_mov_b64_e32 v[4:5], s[16:17]
	v_mad_u64_u32 v[0:1], s[16:17], v2, s63, v[4:5]
	v_mad_i32_i24 v1, v3, s63, v1
	s_waitcnt vmcnt(12)
	v_lshl_add_u64 v[76:77], v[0:1], 0, v[138:139]
	v_add_u32_e32 v0, 0x100, v161
	v_ashrrev_i32_e32 v1, 31, v0
	v_lshrrev_b32_e32 v1, 28, v1
	v_add_u32_e32 v1, v0, v1
	v_ashrrev_i32_e32 v8, 4, v1
	v_and_b32_e32 v1, -16, v1
	s_waitcnt vmcnt(5)
	v_sub_u32_e32 v99, v0, v1
	v_lshlrev_b32_e32 v0, 3, v99
	v_ashrrev_i32_e32 v1, 31, v0
	s_waitcnt vmcnt(3)
	v_lshlrev_b64 v[92:93], 1, v[0:1]
	v_add_u32_e32 v0, 0x200, v161
	v_ashrrev_i32_e32 v1, 31, v0
	v_lshrrev_b32_e32 v1, 28, v1
	v_add_u32_e32 v1, v0, v1
	v_ashrrev_i32_e32 v9, 31, v8
	v_ashrrev_i32_e32 v94, 4, v1
	v_and_b32_e32 v1, -16, v1
	v_lshl_add_u64 v[10:11], s[20:21], 0, v[8:9]
	v_sub_u32_e32 v9, v0, v1
	v_lshlrev_b32_e32 v0, 3, v9
	v_ashrrev_i32_e32 v1, 31, v0
	v_lshlrev_b64 v[100:101], 1, v[0:1]
	v_add_u32_e32 v0, 0x300, v161
	v_ashrrev_i32_e32 v1, 31, v0
	v_lshrrev_b32_e32 v1, 28, v1
	v_add_u32_e32 v1, v0, v1
	v_ashrrev_i32_e32 v102, 4, v1
	v_and_b32_e32 v1, -16, v1
	v_sub_u32_e32 v128, v0, v1
	v_lshlrev_b32_e32 v0, 3, v128
	v_ashrrev_i32_e32 v1, 31, v0
	s_waitcnt vmcnt(0)
	v_lshlrev_b64 v[106:107], 1, v[0:1]
	v_add_u32_e32 v0, 0x400, v161
	v_ashrrev_i32_e32 v1, 31, v0
	v_lshrrev_b32_e32 v1, 28, v1
	v_add_u32_e32 v1, v0, v1
	v_ashrrev_i32_e32 v103, 31, v102
	v_ashrrev_i32_e32 v108, 4, v1
	v_and_b32_e32 v1, -16, v1
	v_lshl_add_u64 v[104:105], s[20:21], 0, v[102:103]
	v_sub_u32_e32 v103, v0, v1
	v_lshlrev_b32_e32 v0, 3, v103
	v_ashrrev_i32_e32 v1, 31, v0
	v_lshlrev_b64 v[112:113], 1, v[0:1]
	v_add_u32_e32 v0, 0x500, v161
	v_ashrrev_i32_e32 v1, 31, v0
	v_lshrrev_b32_e32 v1, 28, v1
	v_add_u32_e32 v1, v0, v1
	v_ashrrev_i32_e32 v109, 31, v108
	v_ashrrev_i32_e32 v114, 4, v1
	v_and_b32_e32 v1, -16, v1
	v_mad_u64_u32 v[6:7], s[16:17], v10, s63, v[4:5]
	v_ashrrev_i32_e32 v95, 31, v94
	v_lshl_add_u64 v[110:111], s[20:21], 0, v[108:109]
	v_sub_u32_e32 v109, v0, v1
	v_mad_i32_i24 v7, v11, s63, v7
	v_lshl_add_u64 v[96:97], s[20:21], 0, v[94:95]
	v_lshlrev_b32_e32 v0, 3, v109
	v_lshl_add_u64 v[78:79], v[6:7], 0, v[92:93]
	v_mad_u64_u32 v[6:7], s[16:17], v96, s63, v[4:5]
	v_ashrrev_i32_e32 v1, 31, v0
	v_mad_i32_i24 v7, v97, s63, v7
	v_lshlrev_b64 v[118:119], 1, v[0:1]
	v_add_u32_e32 v0, 0x600, v161
	v_lshl_add_u64 v[80:81], v[6:7], 0, v[100:101]
	v_mad_u64_u32 v[6:7], s[16:17], v104, s63, v[4:5]
	v_ashrrev_i32_e32 v1, 31, v0
	v_mad_i32_i24 v7, v105, s63, v7
	v_lshrrev_b32_e32 v1, 28, v1
	v_lshl_add_u64 v[82:83], v[6:7], 0, v[106:107]
	v_mad_u64_u32 v[6:7], s[16:17], v110, s63, v[4:5]
	v_ashrrev_i32_e32 v115, 31, v114
	v_add_u32_e32 v1, v0, v1
	v_mad_i32_i24 v7, v111, s63, v7
	v_lshl_add_u64 v[116:117], s[20:21], 0, v[114:115]
	v_ashrrev_i32_e32 v120, 4, v1
	v_and_b32_e32 v1, -16, v1
	v_lshl_add_u64 v[84:85], v[6:7], 0, v[112:113]
	v_mad_u64_u32 v[6:7], s[16:17], v116, s63, v[4:5]
	v_sub_u32_e32 v115, v0, v1
	v_ashrrev_i32_e32 v121, 31, v120
	v_mad_i32_i24 v7, v117, s63, v7
	v_lshlrev_b32_e32 v0, 3, v115
	v_lshl_add_u64 v[122:123], s[20:21], 0, v[120:121]
	v_lshl_add_u64 v[86:87], v[6:7], 0, v[118:119]
	v_mad_u64_u32 v[6:7], s[16:17], v122, s63, v[4:5]
	v_ashrrev_i32_e32 v1, 31, v0
	v_mad_i32_i24 v7, v123, s63, v7
	v_lshlrev_b64 v[124:125], 1, v[0:1]
	v_lshl_add_u64 v[0:1], v[6:7], 0, v[124:125]
	v_add_u32_e32 v6, 0x700, v161
	v_ashrrev_i32_e32 v7, 31, v6
	v_lshrrev_b32_e32 v7, 28, v7
	v_add_u32_e32 v7, v6, v7
	v_ashrrev_i32_e32 v126, 4, v7
	v_and_b32_e32 v7, -16, v7
	v_sub_u32_e32 v121, v6, v7
	v_lshlrev_b32_e32 v6, 3, v121
	v_ashrrev_i32_e32 v127, 31, v126
	v_lshl_add_u64 v[88:89], s[20:21], 0, v[126:127]
	v_ashrrev_i32_e32 v7, 31, v6
	v_mad_u64_u32 v[4:5], s[16:17], v88, s63, v[4:5]
	v_lshlrev_b64 v[90:91], 1, v[6:7]
	v_lshl_or_b32 v6, v137, 2, v130
	v_mad_i32_i24 v5, v89, s63, v5
	v_mul_lo_u32 v6, v6, s69
	v_lshl_add_u64 v[4:5], v[4:5], 0, v[90:91]
	v_lshl_add_u32 v95, v162, 2, v6
	s_barrier
	ds_write2_b32 v95, v12, v48 offset1:16
	ds_write2_b32 v95, v52, v56 offset0:32 offset1:48
	ds_write2_b32 v95, v60, v64 offset0:64 offset1:80
	ds_write2_b32 v95, v68, v72 offset0:96 offset1:112
	ds_write2_b32 v95, v13, v49 offset0:132 offset1:148
	ds_write2_b32 v95, v53, v57 offset0:164 offset1:180
	ds_write2_b32 v95, v61, v65 offset0:196 offset1:212
	ds_write2_b32 v95, v69, v73 offset0:228 offset1:244
	v_add_u32_e32 v12, 0x400, v95
	v_add_co_u32_e32 v4, vcc, s80, v4
	ds_write2_b32 v12, v14, v50 offset0:8 offset1:24
	ds_write2_b32 v12, v54, v58 offset0:40 offset1:56
	v_addc_co_u32_e32 v5, vcc, 0, v5, vcc
	global_load_dwordx4 v[4:7], v[4:5], off offset:512
	ds_write2_b32 v12, v62, v66 offset0:72 offset1:88
	ds_write2_b32 v12, v70, v74 offset0:104 offset1:120
	ds_write2_b32 v12, v15, v51 offset0:140 offset1:156
	ds_write2_b32 v12, v55, v59 offset0:172 offset1:188
	ds_write2_b32 v12, v63, v67 offset0:204 offset1:220
	ds_write2_b32 v12, v71, v75 offset0:236 offset1:252
	v_add_u32_e32 v12, 0x2000, v95
	ds_write2_b32 v12, v16, v20 offset0:64 offset1:80
	ds_write2_b32 v12, v24, v36 offset0:96 offset1:112
	ds_write2_b32 v12, v28, v40 offset0:128 offset1:144
	ds_write2_b32 v12, v44, v32 offset0:160 offset1:176
	ds_write2_b32 v12, v17, v21 offset0:196 offset1:212
	ds_write2_b32 v12, v25, v37 offset0:228 offset1:244
	v_add_u32_e32 v12, 0x2400, v95
	s_add_u32 s12, s12, s14
	ds_write2_b32 v12, v29, v41 offset0:4 offset1:20
	ds_write2_b32 v12, v45, v33 offset0:36 offset1:52
; __device__ __forceinline__ unsigned pack2(float a, float b) { return (unsigned)f2bf(a) | ((unsigned)f2bf(b) << 16); }
; __device__ __forceinline__ float bflo(unsigned w) { return __uint_as_float(w << 16); }
; __device__ __forceinline__ float bfhi(unsigned w) { return __uint_as_float(w & 0xffff0000u); }
; __device__ __forceinline__ float silu_f(float g) { return g / (1.f + __expf(-g)); }
; template <int DH, int MODE>
; __device__ void attn_item(const Params& p, int layer, int b, int blk, int head, char* smem) {
;     ...
;     for (int i = 0; i < NCH; ++i) {
;       int q = tid + 256 * i, r = q / CPR, c = (q % CPR) * 8;
;       gt[i] = *reinterpret_cast<const uint4*>(P + (tq0 + r) * NP + gcol + c);
;     }
;     float lis[2][4];
; #pragma unroll
;     for (int m = 0; m < 2; ++m)
; #pragma unroll
;       for (int j = 0; j < 4; ++j) lis[m][j] = (MODE == 0) ? linv_s[wid * 32 + m * 16 + fq * 4 + j] : 1.f;
;     if (MODE == 0) __syncthreads();
; #pragma unroll
;     for (int m = 0; m < 2; ++m)
; #pragma unroll
;       for (int j = 0; j < 4; ++j) {
;         int r = wid * 32 + m * 16 + fq * 4 + j;
; #pragma unroll
;         for (int n = 0; n < NDT; ++n) Of[r * OST + n * 16 + fr] = o[m][n][j] * lis[m][j];
;       }
;     __syncthreads();
; #pragma unroll
;     for (int i = 0; i < NCH; ++i) {
;       int q = tid + 256 * i, r = q / CPR, c = (q % CPR) * 8;
;       float4 m0 = *reinterpret_cast<const float4*>(Of + r * OST + c);
;       float4 m1 = *reinterpret_cast<const float4*>(Of + r * OST + c + 4);
;       float mm[8] = {m0.x, m0.y, m0.z, m0.w, m1.x, m1.y, m1.z, m1.w};
;       unsigned gw[4] = {gt[i].x, gt[i].y, gt[i].z, gt[i].w};
;       unsigned ow[4];
; #pragma unroll
;       for (int e = 0; e < 4; ++e)
;         ow[e] = pack2(mm[2 * e] * silu_f(bflo(gw[e])), mm[2 * e + 1] * silu_f(bfhi(gw[e])));
	ds_write2_b32 v12, v18, v22 offset0:72 offset1:88
	ds_write2_b32 v12, v26, v38 offset0:104 offset1:120
	ds_write2_b32 v12, v30, v42 offset0:136 offset1:152
	ds_write2_b32 v12, v46, v34 offset0:168 offset1:184
	ds_write2_b32 v12, v19, v23 offset0:204 offset1:220
	ds_write2_b32 v12, v27, v39 offset0:236 offset1:252
	v_add_u32_e32 v12, 0x2800, v95
	s_addc_u32 s13, s13, 0
	ds_write2_b32 v12, v31, v43 offset0:12 offset1:28
	ds_write2_b32 v12, v47, v35 offset0:44 offset1:60
	v_mul_lo_u32 v12, v134, s69
	v_mov_b64_e32 v[14:15], s[12:13]
	v_lshl_add_u32 v98, v136, 2, v12
	v_mad_u64_u32 v[12:13], s[12:13], v2, s70, v[14:15]
	v_mul_lo_u32 v2, v8, s69
	v_mad_i32_i24 v13, v3, s70, v13
	v_lshl_add_u32 v95, v99, 5, v2
	v_mad_u64_u32 v[2:3], s[12:13], v10, s70, v[14:15]
	v_mad_i32_i24 v3, v11, s70, v3
	v_lshl_add_u64 v[26:27], v[2:3], 0, v[92:93]
	v_mul_lo_u32 v2, v94, s69
	v_lshl_add_u32 v93, v9, 5, v2
	v_mad_u64_u32 v[2:3], s[12:13], v96, s70, v[14:15]
	v_mad_i32_i24 v3, v97, s70, v3
	v_lshl_add_u64 v[20:21], v[2:3], 0, v[100:101]
	v_mul_lo_u32 v2, v102, s69
	v_lshl_add_u32 v92, v128, 5, v2
	v_mad_u64_u32 v[2:3], s[12:13], v104, s70, v[14:15]
	v_mad_i32_i24 v3, v105, s70, v3
	v_lshl_add_u64 v[16:17], v[2:3], 0, v[106:107]
	v_mul_lo_u32 v2, v108, s69
	v_lshl_add_u32 v75, v103, 5, v2
	v_mad_u64_u32 v[2:3], s[12:13], v110, s70, v[14:15]
	v_mad_i32_i24 v3, v111, s70, v3
	v_lshl_add_u64 v[30:31], v[12:13], 0, v[138:139]
	v_lshl_add_u64 v[12:13], v[2:3], 0, v[112:113]
	v_mul_lo_u32 v2, v114, s69
	v_lshl_add_u32 v74, v109, 5, v2
	v_mad_u64_u32 v[2:3], s[12:13], v116, s70, v[14:15]
	v_mad_i32_i24 v3, v117, s70, v3
	v_lshl_add_u64 v[10:11], v[2:3], 0, v[118:119]
	v_mul_lo_u32 v2, v120, s69
	v_lshl_add_u32 v73, v115, 5, v2
	v_mad_u64_u32 v[2:3], s[12:13], v122, s70, v[14:15]
	v_mad_i32_i24 v3, v123, s70, v3
	v_add_co_u32_e32 v0, vcc, s80, v0
	v_lshl_add_u64 v[8:9], v[2:3], 0, v[124:125]
	v_mul_lo_u32 v2, v126, s69
	v_addc_co_u32_e32 v1, vcc, 0, v1, vcc
	v_lshl_add_u32 v72, v121, 5, v2
	global_load_dwordx4 v[0:3], v[0:1], off offset:512
	v_mad_u64_u32 v[14:15], s[12:13], v88, s70, v[14:15]
	v_mad_i32_i24 v15, v89, s70, v15
	v_lshl_add_u64 v[14:15], v[14:15], 0, v[90:91]
	s_waitcnt vmcnt(1)
	v_lshlrev_b32_e32 v22, 16, v5
	v_lshlrev_b32_e32 v23, 16, v4
	v_mul_f32_e32 v18, 0xbfb8aa3b, v23
	v_mul_f32_e32 v19, 0xbfb8aa3b, v22
	v_exp_f32_e32 v18, v18
	v_exp_f32_e32 v19, v19
	v_and_b32_e32 v24, 0xffff0000, v5
	v_and_b32_e32 v28, 0xffff0000, v4
	v_mul_f32_e32 v4, 0xbfb8aa3b, v28
	v_pk_add_f32 v[18:19], v[18:19], 1.0 op_sel_hi:[1,0]
	v_exp_f32_e32 v4, v4
	v_and_b32_e32 v34, 0xffff0000, v6
	v_rcp_f32_e32 v19, v19
	s_nop 0
	v_mul_f32_e32 v19, v22, v19
	v_mul_f32_e32 v5, 0xbfb8aa3b, v24
	v_exp_f32_e32 v5, v5
	s_nop 0
	v_pk_add_f32 v[4:5], v[4:5], 1.0 op_sel_hi:[1,0]
	v_rcp_f32_e32 v18, v18
	s_nop 0
	v_mul_f32_e32 v18, v23, v18
	v_lshlrev_b32_e32 v33, 16, v6
	v_rcp_f32_e32 v23, v5
	s_nop 0
	v_mul_f32_e32 v23, v24, v23
	v_lshlrev_b32_e32 v32, 16, v7
	v_mul_f32_e32 v24, 0xbfb8aa3b, v33
	v_mul_f32_e32 v25, 0xbfb8aa3b, v32
	v_exp_f32_e32 v24, v24
	v_exp_f32_e32 v25, v25
	v_rcp_f32_e32 v22, v4
	s_nop 0
	v_mul_f32_e32 v22, v28, v22
	v_and_b32_e32 v28, 0xffff0000, v7
	v_pk_add_f32 v[4:5], v[24:25], 1.0 op_sel_hi:[1,0]
	v_mul_f32_e32 v6, 0xbfb8aa3b, v34
	v_exp_f32_e32 v6, v6
	s_waitcnt vmcnt(0)
	v_lshlrev_b32_e32 v40, 16, v3
	v_lshlrev_b32_e32 v41, 16, v2
	v_rcp_f32_e32 v25, v5
	s_nop 0
	v_mul_f32_e32 v25, v32, v25
	v_mul_f32_e32 v7, 0xbfb8aa3b, v28
	v_exp_f32_e32 v7, v7
	s_nop 0
	v_pk_add_f32 v[6:7], v[6:7], 1.0 op_sel_hi:[1,0]
	v_rcp_f32_e32 v24, v4
	s_nop 0
	v_mul_f32_e32 v24, v33, v24
	v_rcp_f32_e32 v29, v7
	s_nop 0
	v_mul_f32_e32 v29, v28, v29
	v_lshlrev_b32_e32 v32, 16, v1
	v_lshlrev_b32_e32 v36, 16, v0
	v_mul_f32_e32 v4, 0xbfb8aa3b, v36
	v_mul_f32_e32 v5, 0xbfb8aa3b, v32
	v_exp_f32_e32 v4, v4
	v_exp_f32_e32 v5, v5
	v_rcp_f32_e32 v28, v6
	s_nop 0
	v_mul_f32_e32 v28, v34, v28
	v_and_b32_e32 v6, 0xffff0000, v1
	v_pk_add_f32 v[4:5], v[4:5], 1.0 op_sel_hi:[1,0]
	v_and_b32_e32 v34, 0xffff0000, v0
	v_mul_f32_e32 v0, 0xbfb8aa3b, v34
	v_exp_f32_e32 v0, v0
	v_and_b32_e32 v42, 0xffff0000, v3
	v_rcp_f32_e32 v33, v5
	s_nop 0
	v_mul_f32_e32 v33, v32, v33
	v_mul_f32_e32 v1, 0xbfb8aa3b, v6
	v_exp_f32_e32 v1, v1
	s_nop 0
	v_pk_add_f32 v[0:1], v[0:1], 1.0 op_sel_hi:[1,0]
	v_rcp_f32_e32 v32, v4
	s_nop 0
	v_mul_f32_e32 v32, v36, v32
	v_rcp_f32_e32 v35, v1
	s_nop 0
	v_mul_f32_e32 v35, v6, v35
	v_add_co_u32_e64 v4, s[12:13], s80, v86
	s_nop 0
	s_nop 0
	v_addc_co_u32_e64 v5, s[12:13], 0, v87, s[12:13]
	global_load_dwordx4 v[4:7], v[4:5], off offset:512
	v_mul_f32_e32 v36, 0xbfb8aa3b, v41
	v_mul_f32_e32 v37, 0xbfb8aa3b, v40
	v_exp_f32_e32 v36, v36
	v_exp_f32_e32 v37, v37
	v_rcp_f32_e32 v1, v0
	s_nop 0
	v_mul_f32_e32 v34, v34, v1
	v_and_b32_e32 v43, 0xffff0000, v2
	v_pk_add_f32 v[0:1], v[36:37], 1.0 op_sel_hi:[1,0]
	v_mul_f32_e32 v2, 0xbfb8aa3b, v43
	v_exp_f32_e32 v2, v2
	v_rcp_f32_e32 v37, v1
	s_nop 0
	v_mul_f32_e32 v37, v40, v37
	v_mul_f32_e32 v3, 0xbfb8aa3b, v42
	v_exp_f32_e32 v3, v3
	s_nop 0
	v_pk_add_f32 v[38:39], v[2:3], 1.0 op_sel_hi:[1,0]
	v_rcp_f32_e32 v36, v0
	s_nop 0
	v_mul_f32_e32 v36, v41, v36
	v_rcp_f32_e32 v39, v39
	s_nop 0
	v_mul_f32_e32 v39, v42, v39
	v_add_co_u32_e64 v0, s[12:13], s80, v84
	s_waitcnt vmcnt(0)
; __device__ __forceinline__ unsigned pack2(float a, float b) { return (unsigned)f2bf(a) | ((unsigned)f2bf(b) << 16); }
; __device__ __forceinline__ float bflo(unsigned w) { return __uint_as_float(w << 16); }
; __device__ __forceinline__ float bfhi(unsigned w) { return __uint_as_float(w & 0xffff0000u); }
; __device__ __forceinline__ float silu_f(float g) { return g / (1.f + __expf(-g)); }
; template <int DH, int MODE>
; __device__ void attn_item(const Params& p, int layer, int b, int blk, int head, char* smem) {
;     ...
;     for (int i = 0; i < NCH; ++i) {
;       int q = tid + 256 * i, r = q / CPR, c = (q % CPR) * 8;
;       float4 m0 = *reinterpret_cast<const float4*>(Of + r * OST + c);
;       float4 m1 = *reinterpret_cast<const float4*>(Of + r * OST + c + 4);
;       float mm[8] = {m0.x, m0.y, m0.z, m0.w, m1.x, m1.y, m1.z, m1.w};
;       unsigned gw[4] = {gt[i].x, gt[i].y, gt[i].z, gt[i].w};
;       unsigned ow[4];
; #pragma unroll
;       for (int e = 0; e < 4; ++e)
;         ow[e] = pack2(mm[2 * e] * silu_f(bflo(gw[e])), mm[2 * e + 1] * silu_f(bfhi(gw[e])));
	v_lshlrev_b32_e32 v46, 16, v5
	v_lshlrev_b32_e32 v47, 16, v4
	v_mul_f32_e32 v40, 0xbfb8aa3b, v47
	v_mul_f32_e32 v41, 0xbfb8aa3b, v46
	v_exp_f32_e32 v40, v40
	v_exp_f32_e32 v41, v41
	v_addc_co_u32_e64 v1, s[12:13], 0, v85, s[12:13]
	v_rcp_f32_e32 v38, v38
	s_nop 0
	v_mul_f32_e32 v38, v43, v38
	v_pk_add_f32 v[40:41], v[40:41], 1.0 op_sel_hi:[1,0]
	v_and_b32_e32 v42, 0xffff0000, v5
	global_load_dwordx4 v[0:3], v[0:1], off offset:512
	v_and_b32_e32 v48, 0xffff0000, v4
	v_mul_f32_e32 v4, 0xbfb8aa3b, v48
	v_rcp_f32_e32 v41, v41
	s_nop 0
	v_mul_f32_e32 v41, v46, v41
	v_exp_f32_e32 v4, v4
	v_mul_f32_e32 v5, 0xbfb8aa3b, v42
	v_exp_f32_e32 v5, v5
	s_nop 0
	v_pk_add_f32 v[4:5], v[4:5], 1.0 op_sel_hi:[1,0]
	v_rcp_f32_e32 v40, v40
	s_nop 0
	v_mul_f32_e32 v40, v47, v40
	v_lshlrev_b32_e32 v49, 16, v6
	v_rcp_f32_e32 v43, v5
	s_nop 0
	v_mul_f32_e32 v43, v42, v43
	v_lshlrev_b32_e32 v46, 16, v7
	v_mul_f32_e32 v44, 0xbfb8aa3b, v49
	v_mul_f32_e32 v45, 0xbfb8aa3b, v46
	v_exp_f32_e32 v44, v44
	v_exp_f32_e32 v45, v45
	v_rcp_f32_e32 v42, v4
	s_nop 0
	v_mul_f32_e32 v42, v48, v42
	v_and_b32_e32 v47, 0xffff0000, v7
	v_pk_add_f32 v[4:5], v[44:45], 1.0 op_sel_hi:[1,0]
	v_and_b32_e32 v48, 0xffff0000, v6
	v_mul_f32_e32 v6, 0xbfb8aa3b, v48
	v_exp_f32_e32 v6, v6
	v_rcp_f32_e32 v45, v5
	s_nop 0
	v_mul_f32_e32 v45, v46, v45
	v_mul_f32_e32 v7, 0xbfb8aa3b, v47
	v_exp_f32_e32 v7, v7
	s_nop 0
	v_pk_add_f32 v[6:7], v[6:7], 1.0 op_sel_hi:[1,0]
	v_rcp_f32_e32 v44, v4
	s_nop 0
	v_mul_f32_e32 v44, v49, v44
	v_rcp_f32_e32 v4, v7
	s_nop 0
	v_mul_f32_e32 v47, v47, v4
	s_waitcnt vmcnt(0)
	v_lshlrev_b32_e32 v50, 16, v1
	v_lshlrev_b32_e32 v51, 16, v0
	v_mul_f32_e32 v4, 0xbfb8aa3b, v51
	v_mul_f32_e32 v5, 0xbfb8aa3b, v50
	v_exp_f32_e32 v4, v4
	v_exp_f32_e32 v5, v5
	v_rcp_f32_e32 v46, v6
	s_nop 0
	v_mul_f32_e32 v46, v48, v46
	v_and_b32_e32 v6, 0xffff0000, v1
	v_pk_add_f32 v[4:5], v[4:5], 1.0 op_sel_hi:[1,0]
	v_and_b32_e32 v54, 0xffff0000, v0
	v_mul_f32_e32 v0, 0xbfb8aa3b, v54
	v_exp_f32_e32 v0, v0
	v_lshlrev_b32_e32 v58, 16, v2
	v_rcp_f32_e32 v49, v5
	s_nop 0
	v_mul_f32_e32 v49, v50, v49
	v_mul_f32_e32 v1, 0xbfb8aa3b, v6
	v_exp_f32_e32 v1, v1
	s_nop 0
	v_pk_add_f32 v[0:1], v[0:1], 1.0 op_sel_hi:[1,0]
	v_rcp_f32_e32 v48, v4
	s_nop 0
	v_mul_f32_e32 v48, v51, v48
	v_lshlrev_b32_e32 v57, 16, v3
	v_rcp_f32_e32 v51, v1
	s_nop 0
	v_mul_f32_e32 v51, v6, v51
	v_add_co_u32_e64 v4, s[12:13], s80, v82
	s_nop 0
	s_nop 0
	v_addc_co_u32_e64 v5, s[12:13], 0, v83, s[12:13]
	global_load_dwordx4 v[4:7], v[4:5], off offset:512
	v_mul_f32_e32 v50, 0xbfb8aa3b, v58
	v_exp_f32_e32 v52, v50
	v_mul_f32_e32 v50, 0xbfb8aa3b, v57
	v_exp_f32_e32 v53, v50
	v_rcp_f32_e32 v50, v0
	s_nop 0
	v_mul_f32_e32 v50, v54, v50
	v_and_b32_e32 v56, 0xffff0000, v3
	v_pk_add_f32 v[0:1], v[52:53], 1.0 op_sel_hi:[1,0]
	v_and_b32_e32 v59, 0xffff0000, v2
	v_mul_f32_e32 v2, 0xbfb8aa3b, v59
	v_exp_f32_e32 v2, v2
	v_rcp_f32_e32 v53, v1
	s_nop 0
	v_mul_f32_e32 v53, v57, v53
	v_mul_f32_e32 v3, 0xbfb8aa3b, v56
	v_exp_f32_e32 v3, v3
	s_nop 0
	v_pk_add_f32 v[54:55], v[2:3], 1.0 op_sel_hi:[1,0]
	v_rcp_f32_e32 v52, v0
	s_nop 0
	v_mul_f32_e32 v52, v58, v52
	v_rcp_f32_e32 v55, v55
	s_nop 0
	v_mul_f32_e32 v55, v56, v55
	v_add_co_u32_e64 v0, s[12:13], s80, v80
	s_waitcnt vmcnt(0)
	v_lshlrev_b32_e32 v62, 16, v5
	v_lshlrev_b32_e32 v63, 16, v4
	v_mul_f32_e32 v56, 0xbfb8aa3b, v63
	v_mul_f32_e32 v57, 0xbfb8aa3b, v62
	v_exp_f32_e32 v56, v56
	v_exp_f32_e32 v57, v57
	v_addc_co_u32_e64 v1, s[12:13], 0, v81, s[12:13]
	v_rcp_f32_e32 v54, v54
	s_nop 0
	v_mul_f32_e32 v54, v59, v54
	v_pk_add_f32 v[56:57], v[56:57], 1.0 op_sel_hi:[1,0]
	v_and_b32_e32 v58, 0xffff0000, v5
	global_load_dwordx4 v[0:3], v[0:1], off offset:512
	v_and_b32_e32 v64, 0xffff0000, v4
	v_mul_f32_e32 v4, 0xbfb8aa3b, v64
	v_rcp_f32_e32 v57, v57
	s_nop 0
	v_mul_f32_e32 v57, v62, v57
	v_exp_f32_e32 v4, v4
	v_mul_f32_e32 v5, 0xbfb8aa3b, v58
	v_exp_f32_e32 v5, v5
	s_nop 0
	v_pk_add_f32 v[4:5], v[4:5], 1.0 op_sel_hi:[1,0]
	v_rcp_f32_e32 v56, v56
	s_nop 0
	v_mul_f32_e32 v56, v63, v56
	v_lshlrev_b32_e32 v65, 16, v6
	v_rcp_f32_e32 v59, v5
	s_nop 0
	v_mul_f32_e32 v59, v58, v59
	v_lshlrev_b32_e32 v62, 16, v7
	v_mul_f32_e32 v60, 0xbfb8aa3b, v65
	v_mul_f32_e32 v61, 0xbfb8aa3b, v62
	v_exp_f32_e32 v60, v60
	v_exp_f32_e32 v61, v61
	v_rcp_f32_e32 v58, v4
	s_nop 0
	v_mul_f32_e32 v58, v64, v58
	v_and_b32_e32 v63, 0xffff0000, v7
	v_pk_add_f32 v[4:5], v[60:61], 1.0 op_sel_hi:[1,0]
	v_and_b32_e32 v64, 0xffff0000, v6
	v_mul_f32_e32 v6, 0xbfb8aa3b, v64
	v_exp_f32_e32 v6, v6
	v_rcp_f32_e32 v61, v5
	s_nop 0
	v_mul_f32_e32 v61, v62, v61
	v_mul_f32_e32 v7, 0xbfb8aa3b, v63
	v_exp_f32_e32 v7, v7
	s_nop 0
	v_pk_add_f32 v[6:7], v[6:7], 1.0 op_sel_hi:[1,0]
	v_rcp_f32_e32 v60, v4
	s_nop 0
	v_mul_f32_e32 v60, v65, v60
	v_rcp_f32_e32 v4, v7
	s_nop 0
	v_mul_f32_e32 v63, v63, v4
	s_waitcnt vmcnt(0)
	v_lshlrev_b32_e32 v66, 16, v1
	v_lshlrev_b32_e32 v67, 16, v0
	v_mul_f32_e32 v4, 0xbfb8aa3b, v67
	v_mul_f32_e32 v5, 0xbfb8aa3b, v66
	v_exp_f32_e32 v4, v4
	v_exp_f32_e32 v5, v5
	v_and_b32_e32 v68, 0xffff0000, v1
	v_rcp_f32_e32 v62, v6
	s_nop 0
	v_mul_f32_e32 v62, v64, v62
	v_pk_add_f32 v[4:5], v[4:5], 1.0 op_sel_hi:[1,0]
	v_and_b32_e32 v69, 0xffff0000, v0
	v_mul_f32_e32 v0, 0xbfb8aa3b, v69
	v_exp_f32_e32 v6, v0
	v_and_b32_e32 v80, 0xffff0000, v2
	v_rcp_f32_e32 v1, v5
	s_nop 0
	v_mul_f32_e32 v1, v66, v1
	v_mul_f32_e32 v7, 0xbfb8aa3b, v68
	v_exp_f32_e32 v7, v7
	s_nop 0
	v_pk_add_f32 v[64:65], v[6:7], 1.0 op_sel_hi:[1,0]
	v_rcp_f32_e32 v0, v4
	s_nop 0
	v_mul_f32_e32 v0, v67, v0
	v_rcp_f32_e32 v65, v65
	s_nop 0
	v_mul_f32_e32 v65, v68, v65
	v_add_co_u32_e64 v4, s[12:13], s80, v78
	s_nop 0
	s_nop 0
	v_addc_co_u32_e64 v5, s[12:13], 0, v79, s[12:13]
	global_load_dwordx4 v[4:7], v[4:5], off offset:512
	v_lshlrev_b32_e32 v78, 16, v3
	v_lshlrev_b32_e32 v79, 16, v2
	v_mul_f32_e32 v66, 0xbfb8aa3b, v79
	v_mul_f32_e32 v67, 0xbfb8aa3b, v78
	v_exp_f32_e32 v66, v66
	v_exp_f32_e32 v67, v67
	v_and_b32_e32 v70, 0xffff0000, v3
	v_rcp_f32_e32 v64, v64
	s_nop 0
	v_mul_f32_e32 v64, v69, v64
	v_pk_add_f32 v[66:67], v[66:67], 1.0 op_sel_hi:[1,0]
	v_mul_f32_e32 v2, 0xbfb8aa3b, v80
	v_exp_f32_e32 v68, v2
	v_mul_f32_e32 v69, 0xbfb8aa3b, v70
	v_exp_f32_e32 v69, v69
	v_rcp_f32_e32 v3, v67
	s_nop 0
	v_mul_f32_e32 v3, v78, v3
	v_pk_add_f32 v[68:69], v[68:69], 1.0 op_sel_hi:[1,0]
	v_rcp_f32_e32 v2, v66
	s_nop 0
	v_mul_f32_e32 v2, v79, v2
	v_rcp_f32_e32 v67, v69
	s_nop 0
	v_mul_f32_e32 v67, v70, v67
	v_add_co_u32_e64 v70, s[12:13], s80, v76
	s_nop 0
	s_nop 0
	v_addc_co_u32_e64 v71, s[12:13], 0, v77, s[12:13]
	global_load_dwordx4 v[76:79], v[70:71], off offset:512
	v_rcp_f32_e32 v66, v68
	s_nop 0
	v_mul_f32_e32 v66, v80, v66
	s_waitcnt vmcnt(1)
	v_lshlrev_b32_e32 v82, 16, v5
	v_lshlrev_b32_e32 v83, 16, v4
	v_mul_f32_e32 v70, 0xbfb8aa3b, v83
	v_mul_f32_e32 v71, 0xbfb8aa3b, v82
	v_exp_f32_e32 v70, v70
	v_exp_f32_e32 v71, v71
	v_and_b32_e32 v80, 0xffff0000, v5
	v_and_b32_e32 v84, 0xffff0000, v4
	v_mul_f32_e32 v4, 0xbfb8aa3b, v84
	v_pk_add_f32 v[68:69], v[70:71], 1.0 op_sel_hi:[1,0]
	v_exp_f32_e32 v70, v4
	s_waitcnt lgkmcnt(0)
	s_barrier
; __device__ __forceinline__ unsigned pack2(float a, float b) { return (unsigned)f2bf(a) | ((unsigned)f2bf(b) << 16); }
; __device__ __forceinline__ float bflo(unsigned w) { return __uint_as_float(w << 16); }
; __device__ __forceinline__ float bfhi(unsigned w) { return __uint_as_float(w & 0xffff0000u); }
; __device__ __forceinline__ float silu_f(float g) { return g / (1.f + __expf(-g)); }
; template <int DH, int MODE>
; __device__ void attn_item(const Params& p, int layer, int b, int blk, int head, char* smem) {
;     ...
;     for (int i = 0; i < NCH; ++i) {
;       int q = tid + 256 * i, r = q / CPR, c = (q % CPR) * 8;
;       float4 m0 = *reinterpret_cast<const float4*>(Of + r * OST + c);
;       float4 m1 = *reinterpret_cast<const float4*>(Of + r * OST + c + 4);
;       float mm[8] = {m0.x, m0.y, m0.z, m0.w, m1.x, m1.y, m1.z, m1.w};
;       unsigned gw[4] = {gt[i].x, gt[i].y, gt[i].z, gt[i].w};
;       unsigned ow[4];
; #pragma unroll
;       for (int e = 0; e < 4; ++e)
;         ow[e] = pack2(mm[2 * e] * silu_f(bflo(gw[e])), mm[2 * e + 1] * silu_f(bfhi(gw[e])));
;       *reinterpret_cast<uint4*>(Y + (tq0 + r) * YW + ycol + c) = make_uint4(ow[0], ow[1], ow[2], ow[3]);
;     }
	v_mul_f32_e32 v71, 0xbfb8aa3b, v80
	v_exp_f32_e32 v71, v71
	v_rcp_f32_e32 v5, v69
	s_nop 0
	v_mul_f32_e32 v5, v82, v5
	v_pk_add_f32 v[70:71], v[70:71], 1.0 op_sel_hi:[1,0]
	v_rcp_f32_e32 v4, v68
	s_nop 0
	v_mul_f32_e32 v4, v83, v4
	v_rcp_f32_e32 v69, v71
	s_nop 0
	v_mul_f32_e32 v69, v80, v69
	v_lshlrev_b32_e32 v82, 16, v7
	v_lshlrev_b32_e32 v85, 16, v6
	v_mul_f32_e32 v80, 0xbfb8aa3b, v85
	v_mul_f32_e32 v81, 0xbfb8aa3b, v82
	v_exp_f32_e32 v80, v80
	v_exp_f32_e32 v81, v81
	v_rcp_f32_e32 v68, v70
	s_nop 0
	v_mul_f32_e32 v68, v84, v68
	v_and_b32_e32 v83, 0xffff0000, v7
	v_pk_add_f32 v[70:71], v[80:81], 1.0 op_sel_hi:[1,0]
	v_and_b32_e32 v84, 0xffff0000, v6
	v_mul_f32_e32 v6, 0xbfb8aa3b, v84
	v_exp_f32_e32 v80, v6
	s_waitcnt vmcnt(0)
	v_and_b32_e32 v94, 0xffff0000, v78
	v_mul_f32_e32 v81, 0xbfb8aa3b, v83
	v_exp_f32_e32 v81, v81
	v_rcp_f32_e32 v7, v71
	s_nop 0
	v_mul_f32_e32 v7, v82, v7
	v_pk_add_f32 v[80:81], v[80:81], 1.0 op_sel_hi:[1,0]
	v_rcp_f32_e32 v6, v70
	s_nop 0
	v_mul_f32_e32 v6, v85, v6
	v_rcp_f32_e32 v71, v81
	s_nop 0
	v_mul_f32_e32 v71, v83, v71
	v_lshlrev_b32_e32 v86, 16, v77
	v_lshlrev_b32_e32 v87, 16, v76
	v_mul_f32_e32 v82, 0xbfb8aa3b, v87
	v_mul_f32_e32 v83, 0xbfb8aa3b, v86
	v_exp_f32_e32 v82, v82
	v_exp_f32_e32 v83, v83
	v_rcp_f32_e32 v70, v80
	s_nop 0
	v_mul_f32_e32 v70, v84, v70
	v_and_b32_e32 v88, 0xffff0000, v77
	v_pk_add_f32 v[80:81], v[82:83], 1.0 op_sel_hi:[1,0]
	v_and_b32_e32 v83, 0xffff0000, v76
	v_mul_f32_e32 v76, 0xbfb8aa3b, v83
	v_exp_f32_e32 v76, v76
	v_rcp_f32_e32 v85, v81
	s_nop 0
	v_mul_f32_e32 v85, v86, v85
	v_mul_f32_e32 v77, 0xbfb8aa3b, v88
	v_exp_f32_e32 v77, v77
	s_nop 0
	v_pk_add_f32 v[76:77], v[76:77], 1.0 op_sel_hi:[1,0]
	v_rcp_f32_e32 v84, v80
	s_nop 0
	v_mul_f32_e32 v84, v87, v84
	v_rcp_f32_e32 v87, v77
	s_nop 0
	v_mul_f32_e32 v87, v88, v87
	v_lshlrev_b32_e32 v90, 16, v78
	v_lshlrev_b32_e32 v82, 16, v79
	v_mul_f32_e32 v80, 0xbfb8aa3b, v90
	v_mul_f32_e32 v81, 0xbfb8aa3b, v82
	v_exp_f32_e32 v80, v80
	v_exp_f32_e32 v81, v81
	v_rcp_f32_e32 v86, v76
	s_nop 0
	v_mul_f32_e32 v86, v83, v86
	v_and_b32_e32 v83, 0xffff0000, v79
	v_pk_add_f32 v[76:77], v[80:81], 1.0 op_sel_hi:[1,0]
	v_mul_f32_e32 v78, 0xbfb8aa3b, v94
	v_exp_f32_e32 v78, v78
	v_rcp_f32_e32 v89, v77
	s_nop 0
	v_mul_f32_e32 v89, v82, v89
	v_mul_f32_e32 v79, 0xbfb8aa3b, v83
	v_exp_f32_e32 v79, v79
	s_nop 0
	v_pk_add_f32 v[80:81], v[78:79], 1.0 op_sel_hi:[1,0]
	v_rcp_f32_e32 v88, v76
	s_nop 0
	v_mul_f32_e32 v88, v90, v88
	v_rcp_f32_e32 v91, v81
	s_nop 0
	v_mul_f32_e32 v91, v83, v91
	ds_read_b128 v[76:79], v98
	v_rcp_f32_e32 v90, v80
	s_nop 0
	v_mul_f32_e32 v90, v94, v90
	ds_read_b128 v[80:83], v98 offset:16
	v_add_co_u32_e32 v30, vcc, s77, v30
	s_waitcnt lgkmcnt(1)
	v_mov_b32_e32 v96, v76
	v_mov_b32_e32 v97, v78
	v_pk_mul_f32 v[84:85], v[84:85], v[96:97]
	v_mov_b32_e32 v78, v77
	v_pk_mul_f32 v[76:77], v[86:87], v[78:79]
	v_cvt_pk_bf16_f32 v79, 0, v84
	v_cvt_pk_bf16_f32 v78, 0, v85
	v_cvt_pk_bf16_f32 v77, 0, v77
	v_cvt_pk_bf16_f32 v76, 0, v76
	v_and_b32_e32 v77, 0xffff0000, v77
	v_and_b32_e32 v76, 0xffff0000, v76
	v_or_b32_sdwa v77, v77, v78 dst_sel:DWORD dst_unused:UNUSED_PAD src0_sel:DWORD src1_sel:WORD_1
	v_or_b32_sdwa v76, v76, v79 dst_sel:DWORD dst_unused:UNUSED_PAD src0_sel:DWORD src1_sel:WORD_1
	s_waitcnt lgkmcnt(0)
	v_mov_b32_e32 v78, v80
	v_mov_b32_e32 v79, v82
	v_pk_mul_f32 v[78:79], v[88:89], v[78:79]
	v_mov_b32_e32 v82, v81
	v_pk_mul_f32 v[80:81], v[90:91], v[82:83]
	v_cvt_pk_bf16_f32 v78, 0, v78
	v_cvt_pk_bf16_f32 v79, 0, v79
	v_cvt_pk_bf16_f32 v81, 0, v81
	v_cvt_pk_bf16_f32 v80, 0, v80
	v_and_b32_e32 v81, 0xffff0000, v81
	v_and_b32_e32 v80, 0xffff0000, v80
	v_or_b32_sdwa v79, v81, v79 dst_sel:DWORD dst_unused:UNUSED_PAD src0_sel:DWORD src1_sel:WORD_1
	v_or_b32_sdwa v78, v80, v78 dst_sel:DWORD dst_unused:UNUSED_PAD src0_sel:DWORD src1_sel:WORD_1
	ds_read_b128 v[80:83], v95
	v_addc_co_u32_e32 v31, vcc, 0, v31, vcc
	global_store_dwordx4 v[30:31], v[76:79], off offset:2048
	s_nop 0
	ds_read_b128 v[76:79], v95 offset:16
	s_waitcnt lgkmcnt(1)
	v_mov_b32_e32 v30, v80
	v_mov_b32_e32 v31, v82
	v_pk_mul_f32 v[4:5], v[4:5], v[30:31]
	v_mov_b32_e32 v82, v81
	v_pk_mul_f32 v[30:31], v[68:69], v[82:83]
	v_cvt_pk_bf16_f32 v4, 0, v4
	v_cvt_pk_bf16_f32 v5, 0, v5
	v_cvt_pk_bf16_f32 v31, 0, v31
	v_cvt_pk_bf16_f32 v30, 0, v30
	v_and_b32_e32 v31, 0xffff0000, v31
	v_and_b32_e32 v30, 0xffff0000, v30
	v_or_b32_sdwa v5, v31, v5 dst_sel:DWORD dst_unused:UNUSED_PAD src0_sel:DWORD src1_sel:WORD_1
	v_or_b32_sdwa v4, v30, v4 dst_sel:DWORD dst_unused:UNUSED_PAD src0_sel:DWORD src1_sel:WORD_1
	s_waitcnt lgkmcnt(0)
	v_mov_b32_e32 v30, v76
	v_mov_b32_e32 v31, v78
	v_pk_mul_f32 v[6:7], v[6:7], v[30:31]
	v_mov_b32_e32 v78, v77
	v_pk_mul_f32 v[30:31], v[70:71], v[78:79]
	v_cvt_pk_bf16_f32 v6, 0, v6
	v_cvt_pk_bf16_f32 v7, 0, v7
	v_cvt_pk_bf16_f32 v31, 0, v31
	v_cvt_pk_bf16_f32 v30, 0, v30
	ds_read_b128 v[68:71], v93
	v_and_b32_e32 v31, 0xffff0000, v31
	v_and_b32_e32 v30, 0xffff0000, v30
	v_add_co_u32_e32 v26, vcc, s77, v26
	v_or_b32_sdwa v7, v31, v7 dst_sel:DWORD dst_unused:UNUSED_PAD src0_sel:DWORD src1_sel:WORD_1
	v_or_b32_sdwa v6, v30, v6 dst_sel:DWORD dst_unused:UNUSED_PAD src0_sel:DWORD src1_sel:WORD_1
	v_addc_co_u32_e32 v27, vcc, 0, v27, vcc
	global_store_dwordx4 v[26:27], v[4:7], off offset:2048
	s_waitcnt lgkmcnt(0)
	v_mov_b32_e32 v26, v68
	v_mov_b32_e32 v27, v70
	ds_read_b128 v[4:7], v93 offset:16
	v_pk_mul_f32 v[0:1], v[0:1], v[26:27]
	v_mov_b32_e32 v70, v69
	v_pk_mul_f32 v[26:27], v[64:65], v[70:71]
	v_cvt_pk_bf16_f32 v0, 0, v0
	v_cvt_pk_bf16_f32 v1, 0, v1
	v_cvt_pk_bf16_f32 v27, 0, v27
	v_cvt_pk_bf16_f32 v26, 0, v26
	v_and_b32_e32 v27, 0xffff0000, v27
	v_and_b32_e32 v26, 0xffff0000, v26
	v_or_b32_sdwa v1, v27, v1 dst_sel:DWORD dst_unused:UNUSED_PAD src0_sel:DWORD src1_sel:WORD_1
	v_or_b32_sdwa v0, v26, v0 dst_sel:DWORD dst_unused:UNUSED_PAD src0_sel:DWORD src1_sel:WORD_1
	s_waitcnt lgkmcnt(0)
; __device__ __forceinline__ unsigned pack2(float a, float b) { return (unsigned)f2bf(a) | ((unsigned)f2bf(b) << 16); }
; __device__ __forceinline__ float bflo(unsigned w) { return __uint_as_float(w << 16); }
; __device__ __forceinline__ float bfhi(unsigned w) { return __uint_as_float(w & 0xffff0000u); }
; __device__ __forceinline__ float silu_f(float g) { return g / (1.f + __expf(-g)); }
; template <int DH, int MODE>
; __device__ void attn_item(const Params& p, int layer, int b, int blk, int head, char* smem) {
;     ...
;     for (int i = 0; i < NCH; ++i) {
;       int q = tid + 256 * i, r = q / CPR, c = (q % CPR) * 8;
;       float4 m0 = *reinterpret_cast<const float4*>(Of + r * OST + c);
;       float4 m1 = *reinterpret_cast<const float4*>(Of + r * OST + c + 4);
;       float mm[8] = {m0.x, m0.y, m0.z, m0.w, m1.x, m1.y, m1.z, m1.w};
;       unsigned gw[4] = {gt[i].x, gt[i].y, gt[i].z, gt[i].w};
;       unsigned ow[4];
; #pragma unroll
;       for (int e = 0; e < 4; ++e)
;         ow[e] = pack2(mm[2 * e] * silu_f(bflo(gw[e])), mm[2 * e + 1] * silu_f(bfhi(gw[e])));
;       *reinterpret_cast<uint4*>(Y + (tq0 + r) * YW + ycol + c) = make_uint4(ow[0], ow[1], ow[2], ow[3]);
;     }
	v_mov_b32_e32 v26, v4
	v_mov_b32_e32 v27, v6
	v_pk_mul_f32 v[2:3], v[2:3], v[26:27]
	v_mov_b32_e32 v6, v5
	v_pk_mul_f32 v[4:5], v[66:67], v[6:7]
	v_cvt_pk_bf16_f32 v2, 0, v2
	v_cvt_pk_bf16_f32 v3, 0, v3
	v_cvt_pk_bf16_f32 v5, 0, v5
	v_cvt_pk_bf16_f32 v4, 0, v4
	v_and_b32_e32 v5, 0xffff0000, v5
	v_and_b32_e32 v4, 0xffff0000, v4
	v_or_b32_sdwa v3, v5, v3 dst_sel:DWORD dst_unused:UNUSED_PAD src0_sel:DWORD src1_sel:WORD_1
	v_or_b32_sdwa v2, v4, v2 dst_sel:DWORD dst_unused:UNUSED_PAD src0_sel:DWORD src1_sel:WORD_1
	ds_read_b128 v[4:7], v92
	v_add_co_u32_e32 v20, vcc, s77, v20
	s_nop 1
	v_addc_co_u32_e32 v21, vcc, 0, v21, vcc
	global_store_dwordx4 v[20:21], v[0:3], off offset:2048
	s_waitcnt lgkmcnt(0)
	v_mov_b32_e32 v20, v4
	v_mov_b32_e32 v21, v6
	ds_read_b128 v[0:3], v92 offset:16
	v_pk_mul_f32 v[20:21], v[56:57], v[20:21]
	v_mov_b32_e32 v6, v5
	v_pk_mul_f32 v[4:5], v[58:59], v[6:7]
	v_cvt_pk_bf16_f32 v7, 0, v20
	v_cvt_pk_bf16_f32 v6, 0, v21
	v_cvt_pk_bf16_f32 v5, 0, v5
	v_cvt_pk_bf16_f32 v4, 0, v4
	v_and_b32_e32 v5, 0xffff0000, v5
	v_and_b32_e32 v4, 0xffff0000, v4
	v_or_b32_sdwa v5, v5, v6 dst_sel:DWORD dst_unused:UNUSED_PAD src0_sel:DWORD src1_sel:WORD_1
	v_or_b32_sdwa v4, v4, v7 dst_sel:DWORD dst_unused:UNUSED_PAD src0_sel:DWORD src1_sel:WORD_1
	s_waitcnt lgkmcnt(0)
	v_mov_b32_e32 v6, v0
	v_mov_b32_e32 v7, v2
	v_pk_mul_f32 v[6:7], v[60:61], v[6:7]
	v_mov_b32_e32 v2, v1
	v_pk_mul_f32 v[0:1], v[62:63], v[2:3]
	v_cvt_pk_bf16_f32 v3, 0, v6
	v_cvt_pk_bf16_f32 v2, 0, v7
	v_cvt_pk_bf16_f32 v1, 0, v1
	v_cvt_pk_bf16_f32 v0, 0, v0
	v_and_b32_e32 v1, 0xffff0000, v1
	v_and_b32_e32 v0, 0xffff0000, v0
	v_or_b32_sdwa v7, v1, v2 dst_sel:DWORD dst_unused:UNUSED_PAD src0_sel:DWORD src1_sel:WORD_1
	v_or_b32_sdwa v6, v0, v3 dst_sel:DWORD dst_unused:UNUSED_PAD src0_sel:DWORD src1_sel:WORD_1
	ds_read_b128 v[0:3], v75
	v_add_co_u32_e32 v16, vcc, s77, v16
	s_nop 1
	v_addc_co_u32_e32 v17, vcc, 0, v17, vcc
	global_store_dwordx4 v[16:17], v[4:7], off offset:2048
	s_waitcnt lgkmcnt(0)
	v_mov_b32_e32 v16, v0
	v_mov_b32_e32 v17, v2
	ds_read_b128 v[4:7], v75 offset:16
	v_pk_mul_f32 v[16:17], v[48:49], v[16:17]
	v_mov_b32_e32 v2, v1
	v_pk_mul_f32 v[0:1], v[50:51], v[2:3]
	v_cvt_pk_bf16_f32 v3, 0, v16
	v_cvt_pk_bf16_f32 v2, 0, v17
	v_cvt_pk_bf16_f32 v1, 0, v1
	v_cvt_pk_bf16_f32 v0, 0, v0
	v_and_b32_e32 v1, 0xffff0000, v1
	v_and_b32_e32 v0, 0xffff0000, v0
	v_or_b32_sdwa v1, v1, v2 dst_sel:DWORD dst_unused:UNUSED_PAD src0_sel:DWORD src1_sel:WORD_1
	v_or_b32_sdwa v0, v0, v3 dst_sel:DWORD dst_unused:UNUSED_PAD src0_sel:DWORD src1_sel:WORD_1
	s_waitcnt lgkmcnt(0)
	v_mov_b32_e32 v2, v4
	v_mov_b32_e32 v3, v6
	v_pk_mul_f32 v[2:3], v[52:53], v[2:3]
	v_mov_b32_e32 v6, v5
	v_pk_mul_f32 v[4:5], v[54:55], v[6:7]
	v_cvt_pk_bf16_f32 v2, 0, v2
	v_cvt_pk_bf16_f32 v3, 0, v3
	v_cvt_pk_bf16_f32 v5, 0, v5
	v_cvt_pk_bf16_f32 v4, 0, v4
	v_and_b32_e32 v5, 0xffff0000, v5
	v_and_b32_e32 v4, 0xffff0000, v4
	v_or_b32_sdwa v3, v5, v3 dst_sel:DWORD dst_unused:UNUSED_PAD src0_sel:DWORD src1_sel:WORD_1
	v_or_b32_sdwa v2, v4, v2 dst_sel:DWORD dst_unused:UNUSED_PAD src0_sel:DWORD src1_sel:WORD_1
	ds_read_b128 v[4:7], v74
	v_add_co_u32_e32 v12, vcc, s77, v12
	s_nop 1
	v_addc_co_u32_e32 v13, vcc, 0, v13, vcc
	global_store_dwordx4 v[12:13], v[0:3], off offset:2048
	s_waitcnt lgkmcnt(0)
; __device__ __forceinline__ unsigned pack2(float a, float b) { return (unsigned)f2bf(a) | ((unsigned)f2bf(b) << 16); }
; __device__ __forceinline__ float bflo(unsigned w) { return __uint_as_float(w << 16); }
; __device__ __forceinline__ float bfhi(unsigned w) { return __uint_as_float(w & 0xffff0000u); }
; __device__ __forceinline__ float silu_f(float g) { return g / (1.f + __expf(-g)); }
; template <int DH, int MODE>
; __device__ void attn_item(const Params& p, int layer, int b, int blk, int head, char* smem) {
;     ...
;     for (int i = 0; i < NCH; ++i) {
;       int q = tid + 256 * i, r = q / CPR, c = (q % CPR) * 8;
;       float4 m0 = *reinterpret_cast<const float4*>(Of + r * OST + c);
;       float4 m1 = *reinterpret_cast<const float4*>(Of + r * OST + c + 4);
;       float mm[8] = {m0.x, m0.y, m0.z, m0.w, m1.x, m1.y, m1.z, m1.w};
;       unsigned gw[4] = {gt[i].x, gt[i].y, gt[i].z, gt[i].w};
;       unsigned ow[4];
; #pragma unroll
;       for (int e = 0; e < 4; ++e)
;         ow[e] = pack2(mm[2 * e] * silu_f(bflo(gw[e])), mm[2 * e + 1] * silu_f(bfhi(gw[e])));
;       *reinterpret_cast<uint4*>(Y + (tq0 + r) * YW + ycol + c) = make_uint4(ow[0], ow[1], ow[2], ow[3]);
;     }
;   }
;   __syncthreads();
	v_mov_b32_e32 v12, v4
	v_mov_b32_e32 v13, v6
	ds_read_b128 v[0:3], v74 offset:16
	v_pk_mul_f32 v[12:13], v[40:41], v[12:13]
	v_mov_b32_e32 v6, v5
	v_pk_mul_f32 v[4:5], v[42:43], v[6:7]
	v_cvt_pk_bf16_f32 v7, 0, v12
	v_cvt_pk_bf16_f32 v6, 0, v13
	v_cvt_pk_bf16_f32 v5, 0, v5
	v_cvt_pk_bf16_f32 v4, 0, v4
	v_and_b32_e32 v5, 0xffff0000, v5
	v_and_b32_e32 v4, 0xffff0000, v4
	v_or_b32_sdwa v5, v5, v6 dst_sel:DWORD dst_unused:UNUSED_PAD src0_sel:DWORD src1_sel:WORD_1
	v_or_b32_sdwa v4, v4, v7 dst_sel:DWORD dst_unused:UNUSED_PAD src0_sel:DWORD src1_sel:WORD_1
	s_waitcnt lgkmcnt(0)
	v_mov_b32_e32 v6, v0
	v_mov_b32_e32 v7, v2
	v_pk_mul_f32 v[6:7], v[44:45], v[6:7]
	v_mov_b32_e32 v2, v1
	v_pk_mul_f32 v[0:1], v[46:47], v[2:3]
	v_cvt_pk_bf16_f32 v3, 0, v6
	v_cvt_pk_bf16_f32 v2, 0, v7
	v_cvt_pk_bf16_f32 v1, 0, v1
	v_cvt_pk_bf16_f32 v0, 0, v0
	v_and_b32_e32 v1, 0xffff0000, v1
	v_and_b32_e32 v0, 0xffff0000, v0
	v_or_b32_sdwa v7, v1, v2 dst_sel:DWORD dst_unused:UNUSED_PAD src0_sel:DWORD src1_sel:WORD_1
	v_or_b32_sdwa v6, v0, v3 dst_sel:DWORD dst_unused:UNUSED_PAD src0_sel:DWORD src1_sel:WORD_1
	ds_read_b128 v[0:3], v73
	v_add_co_u32_e32 v10, vcc, s77, v10
	s_nop 1
	v_addc_co_u32_e32 v11, vcc, 0, v11, vcc
	global_store_dwordx4 v[10:11], v[4:7], off offset:2048
	s_waitcnt lgkmcnt(0)
	v_mov_b32_e32 v10, v0
	v_mov_b32_e32 v11, v2
	ds_read_b128 v[4:7], v73 offset:16
	v_pk_mul_f32 v[10:11], v[32:33], v[10:11]
	v_mov_b32_e32 v2, v1
	v_pk_mul_f32 v[0:1], v[34:35], v[2:3]
	v_cvt_pk_bf16_f32 v3, 0, v10
	v_cvt_pk_bf16_f32 v2, 0, v11
	v_cvt_pk_bf16_f32 v1, 0, v1
	v_cvt_pk_bf16_f32 v0, 0, v0
	v_and_b32_e32 v1, 0xffff0000, v1
	v_and_b32_e32 v0, 0xffff0000, v0
	v_or_b32_sdwa v1, v1, v2 dst_sel:DWORD dst_unused:UNUSED_PAD src0_sel:DWORD src1_sel:WORD_1
	v_or_b32_sdwa v0, v0, v3 dst_sel:DWORD dst_unused:UNUSED_PAD src0_sel:DWORD src1_sel:WORD_1
	s_waitcnt lgkmcnt(0)
	v_mov_b32_e32 v2, v4
	v_mov_b32_e32 v3, v6
	v_pk_mul_f32 v[2:3], v[36:37], v[2:3]
	v_mov_b32_e32 v6, v5
	v_pk_mul_f32 v[4:5], v[38:39], v[6:7]
	v_cvt_pk_bf16_f32 v2, 0, v2
	v_cvt_pk_bf16_f32 v3, 0, v3
	v_cvt_pk_bf16_f32 v5, 0, v5
	v_cvt_pk_bf16_f32 v4, 0, v4
	v_and_b32_e32 v5, 0xffff0000, v5
	v_and_b32_e32 v4, 0xffff0000, v4
	v_or_b32_sdwa v3, v5, v3 dst_sel:DWORD dst_unused:UNUSED_PAD src0_sel:DWORD src1_sel:WORD_1
	v_or_b32_sdwa v2, v4, v2 dst_sel:DWORD dst_unused:UNUSED_PAD src0_sel:DWORD src1_sel:WORD_1
	ds_read_b128 v[4:7], v72
	v_add_co_u32_e32 v8, vcc, s77, v8
	s_nop 1
	v_addc_co_u32_e32 v9, vcc, 0, v9, vcc
	global_store_dwordx4 v[8:9], v[0:3], off offset:2048
	s_waitcnt lgkmcnt(0)
	v_mov_b32_e32 v8, v4
	v_mov_b32_e32 v9, v6
	ds_read_b128 v[0:3], v72 offset:16
	v_pk_mul_f32 v[8:9], v[18:19], v[8:9]
	v_mov_b32_e32 v6, v5
	v_pk_mul_f32 v[4:5], v[22:23], v[6:7]
	v_cvt_pk_bf16_f32 v7, 0, v8
	v_cvt_pk_bf16_f32 v6, 0, v9
	v_cvt_pk_bf16_f32 v5, 0, v5
	v_cvt_pk_bf16_f32 v4, 0, v4
	v_and_b32_e32 v5, 0xffff0000, v5
	v_and_b32_e32 v4, 0xffff0000, v4
	v_or_b32_sdwa v5, v5, v6 dst_sel:DWORD dst_unused:UNUSED_PAD src0_sel:DWORD src1_sel:WORD_1
	v_or_b32_sdwa v4, v4, v7 dst_sel:DWORD dst_unused:UNUSED_PAD src0_sel:DWORD src1_sel:WORD_1
	s_waitcnt lgkmcnt(0)
	v_mov_b32_e32 v6, v0
	v_mov_b32_e32 v7, v2
	v_pk_mul_f32 v[6:7], v[24:25], v[6:7]
	v_mov_b32_e32 v2, v1
	v_pk_mul_f32 v[0:1], v[28:29], v[2:3]
	v_cvt_pk_bf16_f32 v2, 0, v7
	v_cvt_pk_bf16_f32 v3, 0, v6
	v_cvt_pk_bf16_f32 v0, 0, v0
	v_cvt_pk_bf16_f32 v1, 0, v1
	v_and_b32_e32 v0, 0xffff0000, v0
	v_and_b32_e32 v1, 0xffff0000, v1
	v_or_b32_sdwa v6, v0, v3 dst_sel:DWORD dst_unused:UNUSED_PAD src0_sel:DWORD src1_sel:WORD_1
	v_add_co_u32_e32 v0, vcc, 0x184a1000, v14
	v_or_b32_sdwa v7, v1, v2 dst_sel:DWORD dst_unused:UNUSED_PAD src0_sel:DWORD src1_sel:WORD_1
	s_nop 0
	v_addc_co_u32_e32 v1, vcc, 0, v15, vcc
	global_store_dwordx4 v[0:1], v[4:7], off offset:2048
	s_barrier

; __device__ __forceinline__ float bflo(unsigned w) { return __uint_as_float(w << 16); }
; __device__ __forceinline__ float bfhi(unsigned w) { return __uint_as_float(w & 0xffff0000u); }
; __device__ void gmlp_item(const Params& p, int layer, int b, int n, int g, char* smem) {
;     ...
;   {
;     uint4 raw[8];
; #pragma unroll
;     for (int i = 0; i < 8; ++i) {
;       int q = tid + 256 * i;
;       int st = q & 127, c0 = (q >> 7) * 8;
;       raw[i] = *reinterpret_cast<const uint4*>(P + (t0 + st) * NP + 512 + g * 128 + c0);
;     }
; #pragma unroll
;     for (int i = 0; i < 8; ++i) {
;       int q = tid + 256 * i;
;       int st = q & 127, c0 = (q >> 7) * 8;
;       unsigned w[4] = {raw[i].x, raw[i].y, raw[i].z, raw[i].w};
;       float mu = mu_s[st], rs = rs_s[st];
;       const float4* gp = reinterpret_cast<const float4*>(p.gm_gain + (size_t)layer * 512 + g * 128 + c0);
;       float4 g0 = gp[0], g1 = gp[1];
;       float gg[8] = {g0.x, g0.y, g0.z, g0.w, g1.x, g1.y, g1.z, g1.w};
; #pragma unroll
;       for (int e = 0; e < 8; ++e) {
;         float v = (e & 1) ? bfhi(w[e >> 1]) : bflo(w[e >> 1]);
;         float val = (v - mu) * rs * gg[e];
;         *reinterpret_cast<u16*>(smem + 32768 + (st >> 5) * 8192 + (c0 + e) * 64 + (st & 31) * 2) = f2bf(val);
;       }
;     }
.LBB0_479:
	s_or_b64 exec, exec, s[14:15]
	v_and_b32_e32 v6, 0x7f, v60
	s_ashr_i32 s14, s16, 31
	s_bfe_u32 s20, s82, 0x20003
	s_waitcnt lgkmcnt(0)
	v_or_b32_e32 v0, s36, v6
	s_add_u32 s21, s28, s16
	v_mul_lo_u32 v128, v0, s66
	v_ashrrev_i32_e32 v34, 4, v60
	s_addc_u32 s50, s29, s14
	v_lshl_add_u64 v[0:1], v[128:129], 1, s[12:13]
	s_lshl_b32 s14, s20, 8
	s_mov_b32 s15, s37
	v_and_b32_e32 v2, -8, v34
	v_lshl_add_u64 v[0:1], v[0:1], 0, s[14:15]
	v_ashrrev_i32_e32 v3, 31, v2
	v_lshl_add_u64 v[4:5], v[2:3], 1, v[0:1]
	s_barrier
	global_load_dwordx4 v[28:31], v[4:5], off offset:1024
	s_lshl_b32 s16, s20, 7
	s_lshl_b32 s14, s20, 9
	s_add_u32 s14, s26, s14
	s_addc_u32 s15, s27, 0
	v_lshl_add_u64 v[4:5], v[2:3], 2, s[14:15]
	global_load_dwordx4 v[62:65], v[4:5], off offset:2048
	global_load_dwordx4 v[66:69], v[4:5], off offset:2064
	v_add_u32_e32 v3, 0x100, v60
	v_ashrrev_i32_e32 v48, 4, v3
	v_add_u32_e32 v4, 0x200, v60
	v_lshlrev_b32_e32 v12, 1, v60
	v_and_b32_e32 v82, -8, v48
	v_add_u32_e32 v5, 0x300, v60
	v_lshlrev_b32_e32 v11, 8, v60
	v_ashrrev_i32_e32 v46, 4, v4
	v_and_b32_e32 v4, 62, v12
	v_ashrrev_i32_e32 v83, 31, v82
	v_ashrrev_i32_e32 v44, 4, v5
	v_and_or_b32 v37, v11, s67, v4
	v_lshl_add_u64 v[4:5], v[82:83], 1, v[0:1]
	global_load_dwordx4 v[24:27], v[4:5], off offset:1024
	v_lshl_add_u64 v[4:5], v[82:83], 2, s[14:15]
	global_load_dwordx4 v[70:73], v[4:5], off offset:2064
	global_load_dwordx4 v[74:77], v[4:5], off offset:2048
	v_lshlrev_b32_e32 v3, 2, v6
	v_or_b32_e32 v6, 0x10000, v3
	v_or_b32_e32 v3, 0x10200, v3
	ds_read_b32 v39, v6
	ds_read_b32 v41, v3
	v_add_u32_e32 v7, 0x400, v60
	v_add_u32_e32 v8, 0x500, v60
	v_add_u32_e32 v9, 0x600, v60
	v_add_u32_e32 v10, 0x700, v60
	v_ashrrev_i32_e32 v42, 4, v7
	v_ashrrev_i32_e32 v40, 4, v8
	v_ashrrev_i32_e32 v38, 4, v9
	v_ashrrev_i32_e32 v36, 4, v10
	v_and_b32_e32 v58, -8, v46
	v_and_b32_e32 v56, -8, v44
	v_and_b32_e32 v54, -8, v42
	v_and_b32_e32 v52, -8, v40
	v_and_b32_e32 v50, -8, v38
	v_and_b32_e32 v32, -8, v36
	v_ashrrev_i32_e32 v59, 31, v58
	v_ashrrev_i32_e32 v57, 31, v56
	v_ashrrev_i32_e32 v55, 31, v54
	v_ashrrev_i32_e32 v53, 31, v52
	v_ashrrev_i32_e32 v51, 31, v50
	v_ashrrev_i32_e32 v33, 31, v32
	v_lshl_add_u32 v43, v2, 6, v37
	v_lshl_add_u64 v[2:3], v[58:59], 1, v[0:1]
	v_lshl_add_u64 v[4:5], v[56:57], 1, v[0:1]
	v_lshl_add_u64 v[6:7], v[54:55], 1, v[0:1]
	v_lshl_add_u64 v[8:9], v[52:53], 1, v[0:1]
	v_lshl_add_u64 v[78:79], v[50:51], 1, v[0:1]
	v_lshl_add_u64 v[0:1], v[32:33], 1, v[0:1]
	global_load_dwordx4 v[20:23], v[2:3], off offset:1024
	global_load_dwordx4 v[16:19], v[4:5], off offset:1024
	global_load_dwordx4 v[12:15], v[6:7], off offset:1024
	s_nop 0
	global_load_dwordx4 v[8:11], v[8:9], off offset:1024
	s_nop 0
	global_load_dwordx4 v[4:7], v[78:79], off offset:1024
	s_nop 0
	global_load_dwordx4 v[0:3], v[0:1], off offset:1024
	v_and_b32_e32 v35, 15, v60
	v_lshlrev_b32_e32 v128, 4, v35
	s_waitcnt vmcnt(11)
	v_lshlrev_b32_e32 v45, 16, v28
	s_waitcnt lgkmcnt(1)
	v_sub_f32_e32 v45, v45, v39
	v_and_b32_e32 v28, 0xffff0000, v28
	s_waitcnt lgkmcnt(0)
	v_mul_f32_e32 v45, v41, v45
	v_sub_f32_e32 v28, v28, v39
	s_waitcnt vmcnt(10)
	v_mul_f32_e32 v45, v45, v62
	v_mul_f32_e32 v28, v41, v28
	v_mul_f32_e32 v28, v28, v63
	v_cvt_pk_bf16_f32 v45, 0, v45
	ds_write_b16_d16_hi v43, v45 offset:32768
	v_cvt_pk_bf16_f32 v28, 0, v28
	ds_write_b16_d16_hi v43, v28 offset:32832
	v_lshlrev_b32_e32 v28, 16, v29
	v_sub_f32_e32 v28, v28, v39
	v_mul_f32_e32 v28, v41, v28
	v_mul_f32_e32 v28, v28, v64
	v_cvt_pk_bf16_f32 v28, 0, v28
	ds_write_b16_d16_hi v43, v28 offset:32896
	v_and_b32_e32 v28, 0xffff0000, v29
	v_sub_f32_e32 v28, v28, v39
	v_mul_f32_e32 v28, v41, v28
	v_mul_f32_e32 v28, v28, v65
	v_cvt_pk_bf16_f32 v28, 0, v28
	ds_write_b16_d16_hi v43, v28 offset:32960
	v_lshlrev_b32_e32 v28, 16, v30
	v_sub_f32_e32 v28, v28, v39
	v_mul_f32_e32 v28, v41, v28
	s_waitcnt vmcnt(9)
	v_mul_f32_e32 v28, v28, v66
	v_cvt_pk_bf16_f32 v28, 0, v28
	ds_write_b16_d16_hi v43, v28 offset:33024
	v_and_b32_e32 v28, 0xffff0000, v30
	v_sub_f32_e32 v28, v28, v39
	v_mul_f32_e32 v28, v41, v28
	v_mul_f32_e32 v28, v28, v67
	v_cvt_pk_bf16_f32 v28, 0, v28
	ds_write_b16_d16_hi v43, v28 offset:33088
	v_lshlrev_b32_e32 v28, 16, v31
	v_sub_f32_e32 v30, v28, v39
	v_lshl_add_u64 v[28:29], v[58:59], 2, s[14:15]
	global_load_dwordx4 v[62:65], v[28:29], off offset:2064
	global_load_dwordx4 v[78:81], v[28:29], off offset:2048
	v_mul_f32_e32 v28, v41, v30
	v_mul_f32_e32 v28, v28, v68
	v_cvt_pk_bf16_f32 v28, 0, v28
	ds_write_b16_d16_hi v43, v28 offset:33152
	v_and_b32_e32 v28, 0xffff0000, v31
	v_sub_f32_e32 v28, v28, v39
	v_mul_f32_e32 v28, v41, v28
	v_mul_f32_e32 v28, v28, v69
	v_cvt_pk_bf16_f32 v28, 0, v28
	v_lshl_or_b32 v29, v34, 6, v159
	v_add_u32_e32 v29, v37, v29
	ds_write_b16_d16_hi v29, v28 offset:32768
	s_waitcnt vmcnt(10)
	v_lshlrev_b32_e32 v28, 16, v24
	v_sub_f32_e32 v28, v28, v39
	v_mul_f32_e32 v28, v41, v28
	v_and_b32_e32 v24, 0xffff0000, v24
	s_waitcnt vmcnt(8)
; __device__ __forceinline__ float bflo(unsigned w) { return __uint_as_float(w << 16); }
; __device__ __forceinline__ float bfhi(unsigned w) { return __uint_as_float(w & 0xffff0000u); }
; __device__ void gmlp_item(const Params& p, int layer, int b, int n, int g, char* smem) {
;     ...
; #pragma unroll
;     for (int i = 0; i < 8; ++i) {
;       int q = tid + 256 * i;
;       int st = q & 127, c0 = (q >> 7) * 8;
;       unsigned w[4] = {raw[i].x, raw[i].y, raw[i].z, raw[i].w};
;       float mu = mu_s[st], rs = rs_s[st];
;       const float4* gp = reinterpret_cast<const float4*>(p.gm_gain + (size_t)layer * 512 + g * 128 + c0);
;       float4 g0 = gp[0], g1 = gp[1];
;       float gg[8] = {g0.x, g0.y, g0.z, g0.w, g1.x, g1.y, g1.z, g1.w};
; #pragma unroll
;       for (int e = 0; e < 8; ++e) {
;         float v = (e & 1) ? bfhi(w[e >> 1]) : bflo(w[e >> 1]);
;         float val = (v - mu) * rs * gg[e];
;         *reinterpret_cast<u16*>(smem + 32768 + (st >> 5) * 8192 + (c0 + e) * 64 + (st & 31) * 2) = f2bf(val);
;       }
;     }
	v_mul_f32_e32 v28, v28, v74
	v_sub_f32_e32 v24, v24, v39
	v_mul_f32_e32 v24, v41, v24
	v_cvt_pk_bf16_f32 v28, 0, v28
	v_lshl_add_u32 v43, v82, 6, v37
	v_mul_f32_e32 v24, v24, v75
	ds_write_b16_d16_hi v43, v28 offset:32768
	v_cvt_pk_bf16_f32 v24, 0, v24
	ds_write_b16_d16_hi v43, v24 offset:32832
	v_lshlrev_b32_e32 v24, 16, v25
	v_sub_f32_e32 v24, v24, v39
	v_mul_f32_e32 v24, v41, v24
	v_mul_f32_e32 v24, v24, v76
	v_cvt_pk_bf16_f32 v24, 0, v24
	ds_write_b16_d16_hi v43, v24 offset:32896
	v_and_b32_e32 v24, 0xffff0000, v25
	v_sub_f32_e32 v24, v24, v39
	v_mul_f32_e32 v24, v41, v24
	v_mul_f32_e32 v24, v24, v77
	v_cvt_pk_bf16_f32 v24, 0, v24
	ds_write_b16_d16_hi v43, v24 offset:32960
	v_lshlrev_b32_e32 v24, 16, v26
	v_sub_f32_e32 v24, v24, v39
	v_mul_f32_e32 v24, v41, v24
	v_mul_f32_e32 v24, v24, v70
	v_cvt_pk_bf16_f32 v24, 0, v24
	ds_write_b16_d16_hi v43, v24 offset:33024
	v_and_b32_e32 v24, 0xffff0000, v26
	v_sub_f32_e32 v24, v24, v39
	v_mul_f32_e32 v24, v41, v24
	v_mul_f32_e32 v24, v24, v71
	v_cvt_pk_bf16_f32 v24, 0, v24
	ds_write_b16_d16_hi v43, v24 offset:33088
	v_lshlrev_b32_e32 v24, 16, v27
	v_sub_f32_e32 v26, v24, v39
	v_lshl_add_u64 v[24:25], v[56:57], 2, s[14:15]
	global_load_dwordx4 v[28:31], v[24:25], off offset:2064
	global_load_dwordx4 v[66:69], v[24:25], off offset:2048
	v_mul_f32_e32 v24, v41, v26
	v_mul_f32_e32 v24, v24, v72
	v_cvt_pk_bf16_f32 v24, 0, v24
	ds_write_b16_d16_hi v43, v24 offset:33152
	v_and_b32_e32 v24, 0xffff0000, v27
	v_sub_f32_e32 v24, v24, v39
	v_mul_f32_e32 v24, v41, v24
	v_mul_f32_e32 v24, v24, v73
	v_cvt_pk_bf16_f32 v24, 0, v24
	v_lshl_or_b32 v25, v48, 6, v159
	v_add_u32_e32 v25, v37, v25
	ds_write_b16_d16_hi v25, v24 offset:32768
	s_waitcnt vmcnt(9)
	v_lshlrev_b32_e32 v24, 16, v20
	v_sub_f32_e32 v24, v24, v39
	v_mul_f32_e32 v24, v41, v24
	v_and_b32_e32 v20, 0xffff0000, v20
	s_waitcnt vmcnt(2)
	v_mul_f32_e32 v24, v24, v78
	v_sub_f32_e32 v20, v20, v39
	v_mul_f32_e32 v20, v41, v20
	v_cvt_pk_bf16_f32 v24, 0, v24
	v_lshl_add_u32 v43, v58, 6, v37
	v_mul_f32_e32 v20, v20, v79
	ds_write_b16_d16_hi v43, v24 offset:32768
	v_cvt_pk_bf16_f32 v20, 0, v20
	ds_write_b16_d16_hi v43, v20 offset:32832
	v_lshlrev_b32_e32 v20, 16, v21
	v_sub_f32_e32 v20, v20, v39
	v_mul_f32_e32 v20, v41, v20
	v_mul_f32_e32 v20, v20, v80
	v_cvt_pk_bf16_f32 v20, 0, v20
	ds_write_b16_d16_hi v43, v20 offset:32896
	v_and_b32_e32 v20, 0xffff0000, v21
	v_sub_f32_e32 v20, v20, v39
	v_mul_f32_e32 v20, v41, v20
	v_mul_f32_e32 v20, v20, v81
	v_cvt_pk_bf16_f32 v20, 0, v20
	ds_write_b16_d16_hi v43, v20 offset:32960
	v_lshlrev_b32_e32 v20, 16, v22
	v_sub_f32_e32 v20, v20, v39
	v_mul_f32_e32 v20, v41, v20
	v_mul_f32_e32 v20, v20, v62
	v_cvt_pk_bf16_f32 v20, 0, v20
	ds_write_b16_d16_hi v43, v20 offset:33024
	v_and_b32_e32 v20, 0xffff0000, v22
	v_sub_f32_e32 v20, v20, v39
	v_mul_f32_e32 v20, v41, v20
	v_mul_f32_e32 v20, v20, v63
	v_cvt_pk_bf16_f32 v20, 0, v20
	ds_write_b16_d16_hi v43, v20 offset:33088
	v_lshlrev_b32_e32 v20, 16, v23
	v_sub_f32_e32 v22, v20, v39
	v_lshl_add_u64 v[20:21], v[54:55], 2, s[14:15]
	global_load_dwordx4 v[24:27], v[20:21], off offset:2064
	global_load_dwordx4 v[70:73], v[20:21], off offset:2048
	v_mul_f32_e32 v20, v41, v22
	v_mul_f32_e32 v20, v20, v64
	v_cvt_pk_bf16_f32 v20, 0, v20
	ds_write_b16_d16_hi v43, v20 offset:33152
	v_and_b32_e32 v20, 0xffff0000, v23
	v_sub_f32_e32 v20, v20, v39
	v_mul_f32_e32 v20, v41, v20
	v_mul_f32_e32 v20, v20, v65
	v_cvt_pk_bf16_f32 v20, 0, v20
	v_lshl_or_b32 v21, v46, 6, v159
	v_add_u32_e32 v21, v37, v21
	ds_write_b16_d16_hi v21, v20 offset:32768
	v_lshlrev_b32_e32 v20, 16, v16
	v_sub_f32_e32 v20, v20, v39
	v_mul_f32_e32 v20, v41, v20
	v_and_b32_e32 v16, 0xffff0000, v16
	s_waitcnt vmcnt(2)
	v_mul_f32_e32 v20, v20, v66
	v_sub_f32_e32 v16, v16, v39
	v_mul_f32_e32 v16, v41, v16
	v_cvt_pk_bf16_f32 v20, 0, v20
	v_lshl_add_u32 v43, v56, 6, v37
	v_mul_f32_e32 v16, v16, v67
	ds_write_b16_d16_hi v43, v20 offset:32768
	v_cvt_pk_bf16_f32 v16, 0, v16
	ds_write_b16_d16_hi v43, v16 offset:32832
	v_lshlrev_b32_e32 v16, 16, v17
	v_sub_f32_e32 v16, v16, v39
	v_mul_f32_e32 v16, v41, v16
	v_mul_f32_e32 v16, v16, v68
	v_cvt_pk_bf16_f32 v16, 0, v16
	ds_write_b16_d16_hi v43, v16 offset:32896
	v_and_b32_e32 v16, 0xffff0000, v17
	v_sub_f32_e32 v16, v16, v39
	v_mul_f32_e32 v16, v41, v16
	v_mul_f32_e32 v16, v16, v69
	v_cvt_pk_bf16_f32 v16, 0, v16
	ds_write_b16_d16_hi v43, v16 offset:32960
	v_lshlrev_b32_e32 v16, 16, v18
	v_sub_f32_e32 v16, v16, v39
	v_mul_f32_e32 v16, v41, v16
	v_mul_f32_e32 v16, v16, v28
	v_cvt_pk_bf16_f32 v16, 0, v16
	ds_write_b16_d16_hi v43, v16 offset:33024
	v_and_b32_e32 v16, 0xffff0000, v18
	v_sub_f32_e32 v16, v16, v39
	v_mul_f32_e32 v16, v41, v16
	v_mul_f32_e32 v16, v16, v29
	v_cvt_pk_bf16_f32 v16, 0, v16
	ds_write_b16_d16_hi v43, v16 offset:33088
	v_lshlrev_b32_e32 v16, 16, v19
	v_sub_f32_e32 v18, v16, v39
	v_lshl_add_u64 v[16:17], v[52:53], 2, s[14:15]
	global_load_dwordx4 v[20:23], v[16:17], off offset:2064
	global_load_dwordx4 v[56:59], v[16:17], off offset:2048
	v_mul_f32_e32 v16, v41, v18
	v_mul_f32_e32 v16, v16, v30
	v_cvt_pk_bf16_f32 v16, 0, v16
	ds_write_b16_d16_hi v43, v16 offset:33152
	v_and_b32_e32 v16, 0xffff0000, v19
	v_sub_f32_e32 v16, v16, v39
	v_mul_f32_e32 v16, v41, v16
	v_mul_f32_e32 v16, v16, v31
	v_cvt_pk_bf16_f32 v16, 0, v16
	v_lshl_or_b32 v17, v44, 6, v159
	v_add_u32_e32 v17, v37, v17
	ds_write_b16_d16_hi v17, v16 offset:32768
	v_lshlrev_b32_e32 v16, 16, v12
	v_sub_f32_e32 v16, v16, v39
	v_mul_f32_e32 v16, v41, v16
	v_and_b32_e32 v12, 0xffff0000, v12
	s_waitcnt vmcnt(2)
; __device__ __forceinline__ float bflo(unsigned w) { return __uint_as_float(w << 16); }
; __device__ __forceinline__ float bfhi(unsigned w) { return __uint_as_float(w & 0xffff0000u); }
; __device__ void gmlp_item(const Params& p, int layer, int b, int n, int g, char* smem) {
;     ...
; #pragma unroll
;     for (int i = 0; i < 8; ++i) {
;       int q = tid + 256 * i;
;       int st = q & 127, c0 = (q >> 7) * 8;
;       unsigned w[4] = {raw[i].x, raw[i].y, raw[i].z, raw[i].w};
;       float mu = mu_s[st], rs = rs_s[st];
;       const float4* gp = reinterpret_cast<const float4*>(p.gm_gain + (size_t)layer * 512 + g * 128 + c0);
;       float4 g0 = gp[0], g1 = gp[1];
;       float gg[8] = {g0.x, g0.y, g0.z, g0.w, g1.x, g1.y, g1.z, g1.w};
; #pragma unroll
;       for (int e = 0; e < 8; ++e) {
;         float v = (e & 1) ? bfhi(w[e >> 1]) : bflo(w[e >> 1]);
;         float val = (v - mu) * rs * gg[e];
;         *reinterpret_cast<u16*>(smem + 32768 + (st >> 5) * 8192 + (c0 + e) * 64 + (st & 31) * 2) = f2bf(val);
;       }
;     }
;   }
; #pragma unroll 2
;   for (int i = 0; i < 8; ++i) {
;     int q = tid + 256 * i;
;     int t = q >> 4, cch = q & 15;
;     uint4 v = *reinterpret_cast<const uint4*>(Ws + (size_t)g * 16384 + t * 128 + cch * 8);
;     *reinterpret_cast<uint4*>(smem + (cch >> 2) * 8192 + t * 64 + (cch & 3) * 16) = v;
	v_mul_f32_e32 v16, v16, v70
	v_sub_f32_e32 v12, v12, v39
	v_mul_f32_e32 v12, v41, v12
	v_cvt_pk_bf16_f32 v16, 0, v16
	v_lshl_add_u32 v43, v54, 6, v37
	v_mul_f32_e32 v12, v12, v71
	ds_write_b16_d16_hi v43, v16 offset:32768
	v_cvt_pk_bf16_f32 v12, 0, v12
	ds_write_b16_d16_hi v43, v12 offset:32832
	v_lshlrev_b32_e32 v12, 16, v13
	v_sub_f32_e32 v12, v12, v39
	v_mul_f32_e32 v12, v41, v12
	v_mul_f32_e32 v12, v12, v72
	v_cvt_pk_bf16_f32 v12, 0, v12
	ds_write_b16_d16_hi v43, v12 offset:32896
	v_and_b32_e32 v12, 0xffff0000, v13
	v_sub_f32_e32 v12, v12, v39
	v_mul_f32_e32 v12, v41, v12
	v_mul_f32_e32 v12, v12, v73
	v_cvt_pk_bf16_f32 v12, 0, v12
	ds_write_b16_d16_hi v43, v12 offset:32960
	v_lshlrev_b32_e32 v12, 16, v14
	v_sub_f32_e32 v12, v12, v39
	v_mul_f32_e32 v12, v41, v12
	v_mul_f32_e32 v12, v12, v24
	v_cvt_pk_bf16_f32 v12, 0, v12
	ds_write_b16_d16_hi v43, v12 offset:33024
	v_and_b32_e32 v12, 0xffff0000, v14
	v_sub_f32_e32 v12, v12, v39
	v_mul_f32_e32 v12, v41, v12
	v_mul_f32_e32 v12, v12, v25
	v_cvt_pk_bf16_f32 v12, 0, v12
	ds_write_b16_d16_hi v43, v12 offset:33088
	v_lshlrev_b32_e32 v12, 16, v15
	v_sub_f32_e32 v14, v12, v39
	v_lshl_add_u64 v[12:13], v[50:51], 2, s[14:15]
	global_load_dwordx4 v[16:19], v[12:13], off offset:2064
	global_load_dwordx4 v[28:31], v[12:13], off offset:2048
	v_mul_f32_e32 v12, v41, v14
	v_mul_f32_e32 v12, v12, v26
	v_cvt_pk_bf16_f32 v12, 0, v12
	ds_write_b16_d16_hi v43, v12 offset:33152
	v_and_b32_e32 v12, 0xffff0000, v15
	v_sub_f32_e32 v12, v12, v39
	v_mul_f32_e32 v12, v41, v12
	v_mul_f32_e32 v12, v12, v27
	v_cvt_pk_bf16_f32 v12, 0, v12
	v_lshl_or_b32 v13, v42, 6, v159
	v_add_u32_e32 v13, v37, v13
	ds_write_b16_d16_hi v13, v12 offset:32768
	v_lshlrev_b32_e32 v12, 16, v8
	v_sub_f32_e32 v12, v12, v39
	v_mul_f32_e32 v12, v41, v12
	v_and_b32_e32 v8, 0xffff0000, v8
	s_waitcnt vmcnt(2)
	v_mul_f32_e32 v12, v12, v56
	v_sub_f32_e32 v8, v8, v39
	v_mul_f32_e32 v8, v41, v8
	v_cvt_pk_bf16_f32 v12, 0, v12
	v_lshl_add_u32 v43, v52, 6, v37
	v_mul_f32_e32 v8, v8, v57
	ds_write_b16_d16_hi v43, v12 offset:32768
	v_cvt_pk_bf16_f32 v8, 0, v8
	ds_write_b16_d16_hi v43, v8 offset:32832
	v_lshlrev_b32_e32 v8, 16, v9
	v_sub_f32_e32 v8, v8, v39
	v_mul_f32_e32 v8, v41, v8
	v_mul_f32_e32 v8, v8, v58
	v_cvt_pk_bf16_f32 v8, 0, v8
	ds_write_b16_d16_hi v43, v8 offset:32896
	v_and_b32_e32 v8, 0xffff0000, v9
	v_sub_f32_e32 v8, v8, v39
	v_mul_f32_e32 v8, v41, v8
	v_mul_f32_e32 v8, v8, v59
	v_cvt_pk_bf16_f32 v8, 0, v8
	ds_write_b16_d16_hi v43, v8 offset:32960
	v_lshlrev_b32_e32 v8, 16, v10
	v_sub_f32_e32 v8, v8, v39
	v_mul_f32_e32 v8, v41, v8
	v_mul_f32_e32 v8, v8, v20
	v_cvt_pk_bf16_f32 v8, 0, v8
	ds_write_b16_d16_hi v43, v8 offset:33024
	v_and_b32_e32 v8, 0xffff0000, v10
	v_sub_f32_e32 v8, v8, v39
	v_mul_f32_e32 v8, v41, v8
	v_mul_f32_e32 v8, v8, v21
	v_cvt_pk_bf16_f32 v10, 0, v8
	v_lshl_add_u64 v[8:9], v[32:33], 2, s[14:15]
	global_load_dwordx4 v[12:15], v[8:9], off offset:2064
	global_load_dwordx4 v[24:27], v[8:9], off offset:2048
	v_lshlrev_b32_e32 v8, 16, v11
	v_sub_f32_e32 v8, v8, v39
	v_mul_f32_e32 v8, v41, v8
	v_mul_f32_e32 v8, v8, v22
	v_cvt_pk_bf16_f32 v8, 0, v8
	ds_write_b16_d16_hi v43, v8 offset:33152
	v_and_b32_e32 v8, 0xffff0000, v11
	v_sub_f32_e32 v8, v8, v39
	v_mul_f32_e32 v8, v41, v8
	v_mul_f32_e32 v8, v8, v23
	v_cvt_pk_bf16_f32 v8, 0, v8
	v_lshl_or_b32 v9, v40, 6, v159
	v_add_u32_e32 v9, v37, v9
	ds_write_b16_d16_hi v43, v10 offset:33088
	ds_write_b16_d16_hi v9, v8 offset:32768
	v_lshlrev_b32_e32 v8, 16, v4
	v_sub_f32_e32 v8, v8, v39
	v_mul_f32_e32 v8, v41, v8
	v_and_b32_e32 v4, 0xffff0000, v4
	s_waitcnt vmcnt(2)
	v_mul_f32_e32 v8, v8, v28
	v_sub_f32_e32 v4, v4, v39
	v_mul_f32_e32 v4, v41, v4
	v_cvt_pk_bf16_f32 v8, 0, v8
	v_lshl_add_u32 v9, v50, 6, v37
	v_mul_f32_e32 v4, v4, v29
	ds_write_b16_d16_hi v9, v8 offset:32768
	v_cvt_pk_bf16_f32 v4, 0, v4
	ds_write_b16_d16_hi v9, v4 offset:32832
	v_lshlrev_b32_e32 v4, 16, v5
	v_sub_f32_e32 v4, v4, v39
	v_mul_f32_e32 v4, v41, v4
	v_mul_f32_e32 v4, v4, v30
	v_cvt_pk_bf16_f32 v4, 0, v4
	ds_write_b16_d16_hi v9, v4 offset:32896
	v_and_b32_e32 v4, 0xffff0000, v5
	v_sub_f32_e32 v4, v4, v39
	v_mul_f32_e32 v4, v41, v4
	v_mul_f32_e32 v4, v4, v31
	v_cvt_pk_bf16_f32 v4, 0, v4
	ds_write_b16_d16_hi v9, v4 offset:32960
	v_lshlrev_b32_e32 v4, 16, v6
	v_sub_f32_e32 v4, v4, v39
	v_mul_f32_e32 v4, v41, v4
	v_mul_f32_e32 v4, v4, v16
	v_cvt_pk_bf16_f32 v4, 0, v4
	ds_write_b16_d16_hi v9, v4 offset:33024
	v_and_b32_e32 v4, 0xffff0000, v6
	v_sub_f32_e32 v4, v4, v39
	v_mul_f32_e32 v4, v41, v4
	v_mul_f32_e32 v4, v4, v17
	v_cvt_pk_bf16_f32 v4, 0, v4
	ds_write_b16_d16_hi v9, v4 offset:33088
	v_lshlrev_b32_e32 v4, 16, v7
	v_sub_f32_e32 v4, v4, v39
	v_mul_f32_e32 v4, v41, v4
	v_mul_f32_e32 v4, v4, v18
	v_cvt_pk_bf16_f32 v4, 0, v4
	ds_write_b16_d16_hi v9, v4 offset:33152
	v_and_b32_e32 v4, 0xffff0000, v7
	v_sub_f32_e32 v4, v4, v39
	v_mul_f32_e32 v4, v41, v4
	v_mul_f32_e32 v4, v4, v19
	v_cvt_pk_bf16_f32 v4, 0, v4
	v_lshl_or_b32 v5, v38, 6, v159
	v_add_u32_e32 v5, v37, v5
	ds_write_b16_d16_hi v5, v4 offset:32768
	v_lshlrev_b32_e32 v4, 16, v0
	v_sub_f32_e32 v4, v4, v39
	v_mul_f32_e32 v4, v41, v4
	v_and_b32_e32 v0, 0xffff0000, v0
	s_waitcnt vmcnt(0)
	v_mul_f32_e32 v4, v4, v24
	v_sub_f32_e32 v0, v0, v39
	v_mul_f32_e32 v0, v41, v0
	v_cvt_pk_bf16_f32 v4, 0, v4
	v_lshl_add_u32 v5, v32, 6, v37
	v_mul_f32_e32 v0, v0, v25
	ds_write_b16_d16_hi v5, v4 offset:32768
	v_cvt_pk_bf16_f32 v0, 0, v0
	ds_write_b16_d16_hi v5, v0 offset:32832
	v_lshlrev_b32_e32 v0, 16, v1
	v_sub_f32_e32 v0, v0, v39
	v_mul_f32_e32 v0, v41, v0
	v_mul_f32_e32 v0, v0, v26
	v_cvt_pk_bf16_f32 v0, 0, v0
	ds_write_b16_d16_hi v5, v0 offset:32896
	v_and_b32_e32 v0, 0xffff0000, v1
	v_sub_f32_e32 v0, v0, v39
	v_mul_f32_e32 v0, v41, v0
	v_mul_f32_e32 v0, v0, v27
	v_cvt_pk_bf16_f32 v0, 0, v0
	ds_write_b16_d16_hi v5, v0 offset:32960
	v_lshlrev_b32_e32 v0, 16, v2
	v_sub_f32_e32 v0, v0, v39
	v_mul_f32_e32 v0, v41, v0
	v_mul_f32_e32 v0, v0, v12
	v_cvt_pk_bf16_f32 v0, 0, v0
	ds_write_b16_d16_hi v5, v0 offset:33024
	v_and_b32_e32 v0, 0xffff0000, v2
	v_sub_f32_e32 v0, v0, v39
	v_mul_f32_e32 v0, v41, v0
	v_mul_f32_e32 v0, v0, v13
	v_cvt_pk_bf16_f32 v0, 0, v0
	ds_write_b16_d16_hi v5, v0 offset:33088
	v_lshlrev_b32_e32 v0, 16, v3
	v_sub_f32_e32 v0, v0, v39
	v_mul_f32_e32 v0, v41, v0
	v_mul_f32_e32 v0, v0, v14
	v_cvt_pk_bf16_f32 v0, 0, v0
	ds_write_b16_d16_hi v5, v0 offset:33152
	v_and_b32_e32 v0, 0xffff0000, v3
	v_sub_f32_e32 v0, v0, v39
	v_mul_f32_e32 v0, v41, v0
	v_mul_f32_e32 v0, v0, v15
	s_lshl_b32 s14, s20, 15
	v_cvt_pk_bf16_f32 v0, 0, v0
	v_lshl_or_b32 v1, v36, 6, v159
	s_add_u32 s14, s21, s14
	v_add_u32_e32 v1, v37, v1
	s_addc_u32 s15, s50, 0
	v_lshlrev_b32_e32 v3, 4, v60
	ds_write_b16_d16_hi v1, v0 offset:32768
	v_lshl_add_u64 v[0:1], s[14:15], 0, v[128:129]
	v_lshlrev_b32_e32 v2, 11, v60
	v_and_b32_e32 v3, 48, v3
	v_lshl_add_u64 v[0:1], v[0:1], 0, s[40:41]
	v_and_or_b32 v2, v2, s67, v3
	s_mov_b32 s14, 0
; #define MFMA16(a, b, c) __builtin_amdgcn_mfma_f32_16x16x32_bf16(a, b, c, 0, 0, 0)
; __device__ void gmlp_item(const Params& p, int layer, int b, int n, int g, char* smem) {
;     ...
; #pragma unroll 2
;   for (int i = 0; i < 8; ++i) {
;     int q = tid + 256 * i;
;     int t = q >> 4, cch = q & 15;
;     uint4 v = *reinterpret_cast<const uint4*>(Ws + (size_t)g * 16384 + t * 128 + cch * 8);
;     *reinterpret_cast<uint4*>(smem + (cch >> 2) * 8192 + t * 64 + (cch & 3) * 16) = v;
;   }
;   __syncthreads();
;   f32x4 acc[4][4];
; #pragma unroll
;   for (int m = 0; m < 4; ++m)
; #pragma unroll
;     for (int nn = 0; nn < 4; ++nn) acc[m][nn] = f32x4{0.f, 0.f, 0.f, 0.f};
; #pragma unroll
;   for (int ks = 0; ks < 4; ++ks) {
;     bf16x8 a[4], bb[4];
; #pragma unroll
;     for (int m = 0; m < 4; ++m)
;       a[m] = *reinterpret_cast<const bf16x8*>(smem + ks * 8192 + (wr * 64 + m * 16 + fr) * 64 + fq * 16);
; #pragma unroll
;     for (int nn = 0; nn < 4; ++nn)
;       bb[nn] = *reinterpret_cast<const bf16x8*>(smem + 32768 + ks * 8192 + (wc * 64 + nn * 16 + fr) * 64 + fq * 16);
; #pragma unroll
;     for (int m = 0; m < 4; ++m)
; #pragma unroll
;       for (int nn = 0; nn < 4; ++nn) acc[m][nn] = MFMA16(a[m], bb[nn], acc[m][nn]);
;   }
.LBB0_480:
	v_add_u32_e32 v3, s14, v60
	v_ashrrev_i32_e32 v12, 4, v3
	v_add_u32_e32 v3, 0x100, v3
	v_ashrrev_i32_e32 v3, 4, v3
	v_lshlrev_b32_e32 v4, 7, v12
	v_lshlrev_b32_e32 v6, 7, v3
	v_ashrrev_i32_e32 v5, 31, v4
	v_ashrrev_i32_e32 v7, 31, v6
	v_lshl_add_u64 v[4:5], v[4:5], 1, v[0:1]
	v_lshl_add_u64 v[8:9], v[6:7], 1, v[0:1]
	global_load_dwordx4 v[4:7], v[4:5], off
	s_nop 0
	global_load_dwordx4 v[8:11], v[8:9], off
	s_addk_i32 s14, 0x200
	s_cmpk_lg_i32 s14, 0x800
	v_lshl_add_u32 v12, v12, 6, v2
	v_lshl_add_u32 v3, v3, 6, v2
	s_waitcnt vmcnt(1)
	ds_write_b128 v12, v[4:7]
	s_waitcnt vmcnt(0)
	ds_write_b128 v3, v[8:11]
	s_cbranch_scc1 .LBB0_480
	v_bfe_u32 v32, v60, 4, 2
	v_ashrrev_i32_e32 v33, 7, v60
	v_lshlrev_b32_e32 v4, 4, v32
	v_lshlrev_b32_e32 v0, 12, v33
	v_lshlrev_b32_e32 v5, 6, v35
	v_or3_b32 v37, v4, v0, v5
	s_waitcnt lgkmcnt(0)
	s_barrier
	ds_read_b128 v[0:3], v37
	v_bfe_u32 v39, v60, 6, 1
	v_lshlrev_b32_e32 v6, 12, v39
	v_or3_b32 v41, v4, v6, v5
	ds_read_b128 v[4:7], v41 offset:32768
	ds_read_b128 v[8:11], v37 offset:1024
	ds_read_b128 v[12:15], v41 offset:33792
	ds_read_b128 v[24:27], v41 offset:34816
	ds_read_b128 v[28:31], v41 offset:35840
	s_waitcnt lgkmcnt(4)
	v_mfma_f32_16x16x32_bf16 v[16:19], v[0:3], v[4:7], 0
	s_ashr_i32 s15, s17, 31
	s_add_u32 s14, s28, s17
	s_addc_u32 s15, s29, s15
	s_waitcnt lgkmcnt(2)
	v_mfma_f32_16x16x32_bf16 v[20:23], v[0:3], v[12:15], 0
	v_lshlrev_b32_e32 v33, 6, v33
	s_lshl_b32 s17, s16, 2
	v_lshl_or_b32 v32, v32, 2, v33
	s_waitcnt lgkmcnt(1)
	v_mfma_f32_16x16x32_bf16 v[50:53], v[0:3], v[24:27], 0
	s_add_u32 s20, s24, s17
	s_addc_u32 s21, s25, 0
	v_ashrrev_i32_e32 v33, 31, v32
	s_waitcnt lgkmcnt(0)
	v_mfma_f32_16x16x32_bf16 v[54:57], v[0:3], v[28:31], 0
	ds_read_b128 v[0:3], v37 offset:2048
	ds_read_b128 v[74:77], v37 offset:3072
	ds_read_b128 v[98:101], v37 offset:8192
	v_lshl_add_u64 v[58:59], v[32:33], 2, s[20:21]
	v_mfma_f32_16x16x32_bf16 v[62:65], v[8:11], v[4:7], 0
	v_lshlrev_b32_e32 v33, 2, v35
	v_lshl_or_b32 v126, v39, 8, v33
	v_mad_u64_u32 v[32:33], s[20:21], v32, s69, v[126:127]
	v_mfma_f32_16x16x32_bf16 v[66:69], v[8:11], v[12:15], 0
	v_add_u32_e32 v33, 0x400, v32
	v_ashrrev_i32_e32 v49, 31, v48
	v_ashrrev_i32_e32 v47, 31, v46
	v_mfma_f32_16x16x32_bf16 v[70:73], v[8:11], v[24:27], 0
	v_ashrrev_i32_e32 v45, 31, v44
	v_ashrrev_i32_e32 v43, 31, v42
	v_ashrrev_i32_e32 v39, 31, v38
	v_mfma_f32_16x16x32_bf16 v[8:11], v[8:11], v[28:31], 0
	s_waitcnt lgkmcnt(2)
	v_mfma_f32_16x16x32_bf16 v[78:81], v[0:3], v[4:7], 0
	v_mfma_f32_16x16x32_bf16 v[82:85], v[0:3], v[12:15], 0
	v_mfma_f32_16x16x32_bf16 v[86:89], v[0:3], v[24:27], 0
	v_mfma_f32_16x16x32_bf16 v[90:93], v[0:3], v[28:31], 0
	s_waitcnt lgkmcnt(1)
	v_mfma_f32_16x16x32_bf16 v[94:97], v[74:77], v[4:7], 0
	v_mfma_f32_16x16x32_bf16 v[12:15], v[74:77], v[12:15], 0
	v_mfma_f32_16x16x32_bf16 v[24:27], v[74:77], v[24:27], 0
	v_mfma_f32_16x16x32_bf16 v[0:3], v[74:77], v[28:31], 0
	ds_read_b128 v[28:31], v41 offset:40960
	ds_read_b128 v[74:77], v37 offset:9216
	ds_read_b128 v[102:105], v41 offset:41984
	ds_read_b128 v[106:109], v41 offset:43008
	ds_read_b128 v[4:7], v41 offset:44032
	s_waitcnt lgkmcnt(4)
	v_mfma_f32_16x16x32_bf16 v[16:19], v[98:101], v[28:31], v[16:19]
	s_waitcnt lgkmcnt(2)
	v_mfma_f32_16x16x32_bf16 v[20:23], v[98:101], v[102:105], v[20:23]
	s_waitcnt lgkmcnt(1)
	v_mfma_f32_16x16x32_bf16 v[50:53], v[98:101], v[106:109], v[50:53]
	s_waitcnt lgkmcnt(0)
	v_mfma_f32_16x16x32_bf16 v[54:57], v[98:101], v[4:7], v[54:57]
	ds_read_b128 v[98:101], v37 offset:10240
	v_mfma_f32_16x16x32_bf16 v[62:65], v[74:77], v[28:31], v[62:65]
	v_mfma_f32_16x16x32_bf16 v[66:69], v[74:77], v[102:105], v[66:69]
	v_mfma_f32_16x16x32_bf16 v[70:73], v[74:77], v[106:109], v[70:73]
	v_mfma_f32_16x16x32_bf16 v[8:11], v[74:77], v[4:7], v[8:11]
	ds_read_b128 v[74:77], v37 offset:11264
	ds_read_b128 v[110:113], v37 offset:16384
	ds_read_b128 v[114:117], v37 offset:17408
	ds_read_b128 v[118:121], v37 offset:18432
	ds_read_b128 v[122:125], v37 offset:19456
	ds_read_b128 v[134:137], v41 offset:49152
	ds_read_b128 v[138:141], v41 offset:50176
	ds_read_b128 v[146:149], v41 offset:51200
	ds_read_b128 v[150:153], v41 offset:52224
	ds_read_b128 v[162:165], v37 offset:24576
	ds_read_b128 v[166:169], v37 offset:25600
	s_waitcnt lgkmcnt(11)
	v_mfma_f32_16x16x32_bf16 v[78:81], v[98:101], v[28:31], v[78:81]
	v_mfma_f32_16x16x32_bf16 v[82:85], v[98:101], v[102:105], v[82:85]
	v_mfma_f32_16x16x32_bf16 v[86:89], v[98:101], v[106:109], v[86:89]
	v_mfma_f32_16x16x32_bf16 v[90:93], v[98:101], v[4:7], v[90:93]
	ds_read_b128 v[98:101], v37 offset:26624
	ds_read_b128 v[170:173], v37 offset:27648
	ds_read_b128 v[174:177], v41 offset:57344
	ds_read_b128 v[178:181], v41 offset:58368
	s_waitcnt lgkmcnt(14)
	v_mfma_f32_16x16x32_bf16 v[28:31], v[74:77], v[28:31], v[94:97]
	s_nop 2
	ds_read_b128 v[94:97], v41 offset:59392
	ds_read_b128 v[182:185], v41 offset:60416
	s_waitcnt lgkmcnt(0)
	s_barrier
; #define MFMA16(a, b, c) __builtin_amdgcn_mfma_f32_16x16x32_bf16(a, b, c, 0, 0, 0)
; __device__ void gmlp_item(const Params& p, int layer, int b, int n, int g, char* smem) {
;     ...
;   f32x4 acc[4][4];
; #pragma unroll
;   for (int m = 0; m < 4; ++m)
; #pragma unroll
;     for (int nn = 0; nn < 4; ++nn) acc[m][nn] = f32x4{0.f, 0.f, 0.f, 0.f};
; #pragma unroll
;   for (int ks = 0; ks < 4; ++ks) {
;     bf16x8 a[4], bb[4];
; #pragma unroll
;     for (int m = 0; m < 4; ++m)
;       a[m] = *reinterpret_cast<const bf16x8*>(smem + ks * 8192 + (wr * 64 + m * 16 + fr) * 64 + fq * 16);
; #pragma unroll
;     for (int nn = 0; nn < 4; ++nn)
;       bb[nn] = *reinterpret_cast<const bf16x8*>(smem + 32768 + ks * 8192 + (wc * 64 + nn * 16 + fr) * 64 + fq * 16);
; #pragma unroll
;     for (int m = 0; m < 4; ++m)
; #pragma unroll
;       for (int nn = 0; nn < 4; ++nn) acc[m][nn] = MFMA16(a[m], bb[nn], acc[m][nn]);
;   }
;   __syncthreads();
;   {
;     float* Tf = reinterpret_cast<float*>(smem);
; #pragma unroll
;     for (int m = 0; m < 4; ++m)
; #pragma unroll
;       for (int j = 0; j < 4; ++j) {
;         int t = wr * 64 + m * 16 + fq * 4 + j;
;         float bias = p.gm_b_s[(size_t)layer * 512 + g * 128 + t];
; #pragma unroll
;         for (int nn = 0; nn < 4; ++nn) Tf[t * 132 + wc * 64 + nn * 16 + fr] = acc[m][nn][j] + bias;
;       }
	v_mfma_f32_16x16x32_bf16 v[16:19], v[110:113], v[134:137], v[16:19]
	global_load_dwordx4 v[186:189], v[58:59], off offset:2112
	global_load_dwordx4 v[190:193], v[58:59], off offset:2176
	v_mfma_f32_16x16x32_bf16 v[20:23], v[110:113], v[138:141], v[20:23]
	v_ashrrev_i32_e32 v41, 31, v40
	v_mfma_f32_16x16x32_bf16 v[50:53], v[110:113], v[146:149], v[50:53]
	v_mfma_f32_16x16x32_bf16 v[54:57], v[110:113], v[150:153], v[54:57]
	global_load_dwordx4 v[110:113], v[58:59], off offset:2048
	v_mfma_f32_16x16x32_bf16 v[16:19], v[162:165], v[174:177], v[16:19]
	v_mfma_f32_16x16x32_bf16 v[20:23], v[162:165], v[178:181], v[20:23]
	v_mfma_f32_16x16x32_bf16 v[50:53], v[162:165], v[94:97], v[50:53]
	s_waitcnt vmcnt(0)
	s_nop 4
	v_add_f32_e32 v16, v16, v110
	v_mfma_f32_16x16x32_bf16 v[54:57], v[162:165], v[182:185], v[54:57]
	v_add_f32_e32 v20, v20, v110
	ds_write2_b32 v32, v16, v20 offset1:16
	v_add_f32_e32 v16, v50, v110
	v_add_f32_e32 v35, v53, v113
	v_mfma_f32_16x16x32_bf16 v[62:65], v[114:117], v[134:137], v[62:65]
	s_nop 2
	v_add_f32_e32 v20, v54, v110
	ds_write2_b32 v32, v16, v20 offset0:32 offset1:48
	v_add_f32_e32 v16, v17, v111
	v_add_f32_e32 v17, v21, v111
	ds_write2_b32 v32, v16, v17 offset0:132 offset1:148
	v_add_f32_e32 v16, v51, v111
	v_add_f32_e32 v17, v55, v111
	ds_write2_b32 v32, v16, v17 offset0:164 offset1:180
	v_add_f32_e32 v16, v18, v112
	v_add_f32_e32 v17, v22, v112
	ds_write2_b32 v33, v16, v17 offset0:8 offset1:24
	v_add_f32_e32 v16, v52, v112
	global_load_dwordx4 v[50:53], v[58:59], off offset:2240
	v_mfma_f32_16x16x32_bf16 v[66:69], v[114:117], v[138:141], v[66:69]
	v_add_f32_e32 v17, v56, v112
	v_add_f32_e32 v20, v19, v113
	v_add_f32_e32 v21, v23, v113
	v_mfma_f32_16x16x32_bf16 v[70:73], v[114:117], v[146:149], v[70:73]
	ds_write2_b32 v33, v16, v17 offset0:40 offset1:56
	ds_write2_b32 v33, v20, v21 offset0:140 offset1:156
	v_add_f32_e32 v37, v57, v113
	v_mfma_f32_16x16x32_bf16 v[8:11], v[114:117], v[150:153], v[8:11]
	ds_write2_b32 v33, v35, v37 offset0:172 offset1:188
	v_add_u32_e32 v33, 0x2000, v32
	v_ashrrev_i32_e32 v35, 31, v34
	v_mfma_f32_16x16x32_bf16 v[16:19], v[166:169], v[174:177], v[62:65]
	v_ashrrev_i32_e32 v37, 31, v36
	v_lshl_add_u64 v[58:59], v[42:43], 0, s[36:37]
	v_mfma_f32_16x16x32_bf16 v[20:23], v[166:169], v[178:181], v[66:69]
	v_mfma_f32_16x16x32_bf16 v[54:57], v[166:169], v[94:97], v[70:73]
	s_nop 3
	v_add_f32_e32 v16, v16, v186
	s_nop 1
	v_add_f32_e32 v20, v20, v186
	ds_write2_b32 v33, v16, v20 offset0:64 offset1:80
	v_mfma_f32_16x16x32_bf16 v[8:11], v[166:169], v[182:185], v[8:11]
	v_add_u32_e32 v20, 0x2400, v32
	v_add_f32_e32 v16, v54, v186
	v_mfma_f32_16x16x32_bf16 v[62:65], v[118:121], v[134:137], v[78:81]
	v_mfma_f32_16x16x32_bf16 v[66:69], v[118:121], v[138:141], v[82:85]
	s_nop 3
	v_add_f32_e32 v8, v8, v186
	ds_write2_b32 v33, v16, v8 offset0:96 offset1:112
	v_add_f32_e32 v8, v17, v187
	v_add_f32_e32 v16, v21, v187
	ds_write2_b32 v33, v8, v16 offset0:196 offset1:212
	v_add_f32_e32 v8, v55, v187
	v_add_f32_e32 v9, v9, v187
	ds_write2_b32 v33, v8, v9 offset0:228 offset1:244
	v_add_f32_e32 v8, v18, v188
	v_add_f32_e32 v9, v22, v188
	v_mfma_f32_16x16x32_bf16 v[70:73], v[118:121], v[146:149], v[86:89]
	ds_write2_b32 v20, v8, v9 offset0:72 offset1:88
	v_add_f32_e32 v8, v56, v188
	v_add_f32_e32 v9, v10, v188
	v_mfma_f32_16x16x32_bf16 v[78:81], v[118:121], v[150:153], v[90:93]
	ds_write2_b32 v20, v8, v9 offset0:104 offset1:120
	v_add_f32_e32 v8, v19, v189
	v_add_f32_e32 v9, v23, v189
	v_mfma_f32_16x16x32_bf16 v[16:19], v[98:101], v[174:177], v[62:65]
	ds_write2_b32 v20, v8, v9 offset0:204 offset1:220
	v_add_f32_e32 v21, v57, v189
	v_add_f32_e32 v22, v11, v189
	v_mfma_f32_16x16x32_bf16 v[8:11], v[98:101], v[178:181], v[66:69]
	ds_write2_b32 v20, v21, v22 offset0:236 offset1:252
	s_nop 2
	v_add_f32_e32 v16, v16, v190
	v_add_u32_e32 v33, 0x4000, v32
	v_mfma_f32_16x16x32_bf16 v[20:23], v[98:101], v[94:97], v[70:73]
	v_lshl_add_u64 v[62:63], v[38:39], 0, s[36:37]
	v_add_f32_e32 v8, v8, v190
	ds_write2_b32 v33, v16, v8 offset0:128 offset1:144
	v_mfma_f32_16x16x32_bf16 v[54:57], v[98:101], v[182:185], v[78:81]
	v_add_f32_e32 v10, v10, v192
	s_nop 2
	v_add_f32_e32 v8, v20, v190
	v_mfma_f32_16x16x32_bf16 v[12:15], v[74:77], v[102:105], v[12:15]
	v_mfma_f32_16x16x32_bf16 v[24:27], v[74:77], v[106:109], v[24:27]
	s_nop 0
	v_add_f32_e32 v16, v54, v190
	ds_write2_b32 v33, v8, v16 offset0:160 offset1:176
	v_add_f32_e32 v8, v17, v191
	v_mfma_f32_16x16x32_bf16 v[0:3], v[74:77], v[4:7], v[0:3]
	v_add_f32_e32 v4, v9, v191
	v_add_u32_e32 v9, 0x4400, v32
	ds_write2_b32 v9, v8, v4 offset0:4 offset1:20
	v_mfma_f32_16x16x32_bf16 v[4:7], v[122:125], v[134:137], v[28:31]
	v_add_f32_e32 v8, v21, v191
	v_add_f32_e32 v16, v55, v191
	ds_write2_b32 v9, v8, v16 offset0:36 offset1:52
	v_mfma_f32_16x16x32_bf16 v[12:15], v[122:125], v[138:141], v[12:15]
	v_add_f32_e32 v8, v18, v192
	ds_write2_b32 v9, v8, v10 offset0:136 offset1:152
	v_add_f32_e32 v8, v22, v192
	v_mfma_f32_16x16x32_bf16 v[24:27], v[122:125], v[146:149], v[24:27]
	v_add_f32_e32 v10, v56, v192
	ds_write2_b32 v9, v8, v10 offset0:168 offset1:184
	v_add_f32_e32 v8, v19, v193
	v_mfma_f32_16x16x32_bf16 v[0:3], v[122:125], v[150:153], v[0:3]
	v_add_f32_e32 v9, v11, v193
	v_add_u32_e32 v16, 0x4800, v32
	ds_write2_b32 v16, v8, v9 offset0:12 offset1:28
	v_mfma_f32_16x16x32_bf16 v[4:7], v[170:173], v[174:177], v[4:7]
	v_add_f32_e32 v17, v23, v193
	v_add_f32_e32 v18, v57, v193
	ds_write2_b32 v16, v17, v18 offset0:44 offset1:60
	v_mfma_f32_16x16x32_bf16 v[8:11], v[170:173], v[178:181], v[12:15]
	v_add_u32_e32 v16, 0x6000, v32
	s_waitcnt vmcnt(0)
; __device__ __forceinline__ unsigned pack2(float a, float b) { return (unsigned)f2bf(a) | ((unsigned)f2bf(b) << 16); }
; __device__ __forceinline__ float bflo(unsigned w) { return __uint_as_float(w << 16); }
; __device__ __forceinline__ float bfhi(unsigned w) { return __uint_as_float(w & 0xffff0000u); }
; __device__ __forceinline__ float silu_f(float g) { return g / (1.f + __expf(-g)); }
; __device__ void gmlp_item(const Params& p, int layer, int b, int n, int g, char* smem) {
;     ...
;   __syncthreads();
;   {
;     float* Tf = reinterpret_cast<float*>(smem);
; #pragma unroll
;     for (int m = 0; m < 4; ++m)
; #pragma unroll
;       for (int j = 0; j < 4; ++j) {
;         int t = wr * 64 + m * 16 + fq * 4 + j;
;         float bias = p.gm_b_s[(size_t)layer * 512 + g * 128 + t];
; #pragma unroll
;         for (int nn = 0; nn < 4; ++nn) Tf[t * 132 + wc * 64 + nn * 16 + fr] = acc[m][nn][j] + bias;
;       }
;     __syncthreads();
;     uint4 uu[8], gt[8];
; #pragma unroll
;     for (int i = 0; i < 8; ++i) {
;       int q = tid + 256 * i, t = q >> 4, c = (q & 15) * 8;
;       uu[i] = *reinterpret_cast<const uint4*>(P + (t0 + t) * NP + g * 128 + c);
;       gt[i] = *reinterpret_cast<const uint4*>(P + (t0 + t) * NP + 1024 + g * 128 + c);
;     }
; #pragma unroll
;     for (int i = 0; i < 8; ++i) {
;       int q = tid + 256 * i, t = q >> 4, c = (q & 15) * 8;
;       float4 m0 = *reinterpret_cast<const float4*>(Tf + t * 132 + c);
;       float4 m1 = *reinterpret_cast<const float4*>(Tf + t * 132 + c + 4);
;       float mm[8] = {m0.x, m0.y, m0.z, m0.w, m1.x, m1.y, m1.z, m1.w};
;       unsigned uw[4] = {uu[i].x, uu[i].y, uu[i].z, uu[i].w};
;       unsigned gw[4] = {gt[i].x, gt[i].y, gt[i].z, gt[i].w};
;       unsigned ow[4];
; #pragma unroll
;       for (int e = 0; e < 4; ++e) {
;         float y0 = bflo(uw[e]) * mm[2 * e] * silu_f(bflo(gw[e]));
;         float y1 = bfhi(uw[e]) * mm[2 * e + 1] * silu_f(bfhi(gw[e]));
;         ow[e] = pack2(y0, y1);
;       }
;       *reinterpret_cast<uint4*>(Y + (t0 + t) * YW + g * 128 + c) = make_uint4(ow[0], ow[1], ow[2], ow[3]);
;     }
	s_nop 1
	v_add_f32_e32 v4, v4, v50
	v_lshl_add_u64 v[56:57], v[36:37], 0, s[36:37]
	v_mfma_f32_16x16x32_bf16 v[12:15], v[170:173], v[94:97], v[24:27]
	v_lshl_add_u64 v[20:21], v[44:45], 0, s[36:37]
	v_add_f32_e32 v8, v8, v50
	ds_write2_b32 v16, v4, v8 offset0:192 offset1:208
	v_mfma_f32_16x16x32_bf16 v[0:3], v[170:173], v[182:185], v[0:3]
	s_nop 3
	v_add_f32_e32 v4, v12, v50
	s_nop 2
	v_add_f32_e32 v0, v0, v50
	ds_write2_b32 v16, v4, v0 offset0:224 offset1:240
	v_add_f32_e32 v0, v5, v51
	v_add_f32_e32 v4, v9, v51
	v_add_u32_e32 v5, 0x6400, v32
	ds_write2_b32 v5, v0, v4 offset0:68 offset1:84
	v_add_f32_e32 v0, v13, v51
	v_add_f32_e32 v1, v1, v51
	ds_write2_b32 v5, v0, v1 offset0:100 offset1:116
	v_add_f32_e32 v0, v6, v52
	v_add_f32_e32 v1, v10, v52
	ds_write2_b32 v5, v0, v1 offset0:200 offset1:216
	v_add_f32_e32 v0, v14, v52
	v_add_f32_e32 v1, v2, v52
	ds_write2_b32 v5, v0, v1 offset0:232 offset1:248
	v_add_f32_e32 v0, v7, v53
	v_add_f32_e32 v1, v11, v53
	v_add_u32_e32 v2, 0x6800, v32
	ds_write2_b32 v2, v0, v1 offset0:76 offset1:92
	v_add_f32_e32 v0, v15, v53
	v_add_f32_e32 v1, v3, v53
	ds_write2_b32 v2, v0, v1 offset0:108 offset1:124
	v_lshlrev_b32_e32 v0, 3, v60
	v_lshl_add_u64 v[8:9], v[34:35], 0, s[36:37]
	v_mov_b64_e32 v[10:11], s[12:13]
	v_and_b32_e32 v24, 0x78, v0
	v_mad_u64_u32 v[0:1], s[12:13], v8, s63, v[10:11]
	v_mad_i32_i24 v1, v9, s63, v1
	s_lshl_b32 s12, s16, 1
	s_mov_b32 s13, s37
	v_lshl_add_u64 v[0:1], v[0:1], 0, s[12:13]
	v_lshlrev_b32_e32 v128, 1, v24
	v_lshl_add_u64 v[12:13], v[48:49], 0, s[36:37]
	v_lshl_add_u64 v[52:53], v[0:1], 0, v[128:129]
	v_mad_u64_u32 v[0:1], s[16:17], v12, s63, v[10:11]
	v_mad_i32_i24 v1, v13, s63, v1
	v_lshl_add_u64 v[0:1], v[0:1], 0, s[12:13]
	v_lshl_add_u64 v[32:33], v[0:1], 0, v[128:129]
	v_mad_u64_u32 v[0:1], s[16:17], v56, s63, v[10:11]
	v_mad_i32_i24 v1, v57, s63, v1
	v_lshl_add_u64 v[0:1], v[0:1], 0, s[12:13]
	v_lshl_add_u64 v[4:5], v[0:1], 0, v[128:129]
	s_waitcnt lgkmcnt(0)
	s_barrier
	global_load_dwordx4 v[0:3], v[4:5], off
	s_nop 0
	global_load_dwordx4 v[4:7], v[4:5], off offset:2048
	v_lshl_add_u64 v[16:17], v[46:47], 0, s[36:37]
	v_mad_u64_u32 v[14:15], s[16:17], v16, s63, v[10:11]
	v_mad_i32_i24 v15, v17, s63, v15
	v_lshl_add_u64 v[14:15], v[14:15], 0, s[12:13]
	v_lshl_add_u64 v[30:31], v[14:15], 0, v[128:129]
	v_mad_u64_u32 v[14:15], s[16:17], v20, s63, v[10:11]
	v_mad_i32_i24 v15, v21, s63, v15
	v_lshl_add_u64 v[14:15], v[14:15], 0, s[12:13]
	v_lshl_add_u64 v[26:27], v[14:15], 0, v[128:129]
	v_mad_u64_u32 v[14:15], s[16:17], v58, s63, v[10:11]
	v_mad_i32_i24 v15, v59, s63, v15
	v_lshl_add_u64 v[14:15], v[14:15], 0, s[12:13]
	v_lshl_add_u64 v[60:61], v[40:41], 0, s[36:37]
	v_lshl_add_u64 v[22:23], v[14:15], 0, v[128:129]
	v_mad_u64_u32 v[14:15], s[16:17], v60, s63, v[10:11]
	v_mad_u64_u32 v[10:11], s[16:17], v62, s63, v[10:11]
	v_mad_i32_i24 v15, v61, s63, v15
	v_mad_i32_i24 v11, v63, s63, v11
	v_lshl_add_u64 v[14:15], v[14:15], 0, s[12:13]
	v_lshl_add_u64 v[10:11], v[10:11], 0, s[12:13]
	s_add_u32 s12, s14, s12
	s_addc_u32 s13, s15, 0
	v_lshl_add_u64 v[18:19], v[14:15], 0, v[128:129]
	v_lshl_add_u64 v[14:15], v[10:11], 0, v[128:129]
	v_lshlrev_b32_e32 v10, 2, v24
	v_lshl_add_u64 v[24:25], s[12:13], 0, v[128:129]
	v_lshl_add_u64 v[64:65], v[24:25], 0, s[42:43]
	v_mad_u64_u32 v[54:55], s[12:13], v34, s69, v[10:11]
	v_mad_u64_u32 v[34:35], s[12:13], v48, s69, v[10:11]
	v_mad_u64_u32 v[48:49], s[12:13], v12, s70, v[64:65]
	v_mad_u64_u32 v[28:29], s[12:13], v46, s69, v[10:11]
	v_mad_u64_u32 v[46:47], s[12:13], v16, s70, v[64:65]
	v_mad_u64_u32 v[50:51], s[12:13], v8, s70, v[64:65]
	v_mad_i32_i24 v49, v13, s70, v49
	v_mad_i32_i24 v47, v17, s70, v47
	v_mad_u64_u32 v[24:25], s[12:13], v44, s69, v[10:11]
	v_mad_u64_u32 v[44:45], s[12:13], v20, s70, v[64:65]
	v_mad_u64_u32 v[16:17], s[12:13], v40, s69, v[10:11]
	v_mad_u64_u32 v[12:13], s[12:13], v38, s69, v[10:11]
	v_mad_i32_i24 v51, v9, s70, v51
	v_mad_i32_i24 v45, v21, s70, v45
	v_mad_u64_u32 v[20:21], s[12:13], v42, s69, v[10:11]
	v_mad_u64_u32 v[8:9], s[12:13], v36, s69, v[10:11]
	v_mad_u64_u32 v[40:41], s[12:13], v60, s70, v[64:65]
	v_mad_i32_i24 v41, v61, s70, v41
	v_mad_u64_u32 v[42:43], s[12:13], v58, s70, v[64:65]
	v_mad_u64_u32 v[36:37], s[12:13], v56, s70, v[64:65]
	v_mad_i32_i24 v43, v59, s70, v43
	v_mad_i32_i24 v37, v57, s70, v37
	v_mad_u64_u32 v[38:39], s[12:13], v62, s70, v[64:65]
	v_mad_i32_i24 v39, v63, s70, v39
	s_waitcnt vmcnt(1)
	v_lshlrev_b32_e32 v63, 16, v1
	s_waitcnt vmcnt(0)
	v_lshlrev_b32_e32 v13, 16, v5
	v_lshlrev_b32_e32 v17, 16, v4
	v_mul_f32_e32 v9, 0xbfb8aa3b, v17
	v_and_b32_e32 v21, 0xffff0000, v5
	v_mul_f32_e32 v5, 0xbfb8aa3b, v13
	v_exp_f32_e32 v60, v9
	v_exp_f32_e32 v61, v5
	ds_read_b128 v[56:59], v8
	ds_read_b128 v[8:11], v8 offset:16
	v_and_b32_e32 v25, 0xffff0000, v4
	v_mul_f32_e32 v4, 0xbfb8aa3b, v25
	v_pk_add_f32 v[60:61], v[60:61], 1.0 op_sel_hi:[1,0]
	s_waitcnt lgkmcnt(1)
; __device__ __forceinline__ unsigned pack2(float a, float b) { return (unsigned)f2bf(a) | ((unsigned)f2bf(b) << 16); }
; __device__ __forceinline__ float bflo(unsigned w) { return __uint_as_float(w << 16); }
; __device__ __forceinline__ float bfhi(unsigned w) { return __uint_as_float(w & 0xffff0000u); }
; __device__ __forceinline__ float silu_f(float g) { return g / (1.f + __expf(-g)); }
; __device__ void gmlp_item(const Params& p, int layer, int b, int n, int g, char* smem) {
;     ...
;     uint4 uu[8], gt[8];
; #pragma unroll
;     for (int i = 0; i < 8; ++i) {
;       int q = tid + 256 * i, t = q >> 4, c = (q & 15) * 8;
;       uu[i] = *reinterpret_cast<const uint4*>(P + (t0 + t) * NP + g * 128 + c);
;       gt[i] = *reinterpret_cast<const uint4*>(P + (t0 + t) * NP + 1024 + g * 128 + c);
;     }
; #pragma unroll
;     for (int i = 0; i < 8; ++i) {
;       int q = tid + 256 * i, t = q >> 4, c = (q & 15) * 8;
;       float4 m0 = *reinterpret_cast<const float4*>(Tf + t * 132 + c);
;       float4 m1 = *reinterpret_cast<const float4*>(Tf + t * 132 + c + 4);
;       float mm[8] = {m0.x, m0.y, m0.z, m0.w, m1.x, m1.y, m1.z, m1.w};
;       unsigned uw[4] = {uu[i].x, uu[i].y, uu[i].z, uu[i].w};
;       unsigned gw[4] = {gt[i].x, gt[i].y, gt[i].z, gt[i].w};
;       unsigned ow[4];
; #pragma unroll
;       for (int e = 0; e < 4; ++e) {
;         float y0 = bflo(uw[e]) * mm[2 * e] * silu_f(bflo(gw[e]));
;         float y1 = bfhi(uw[e]) * mm[2 * e + 1] * silu_f(bfhi(gw[e]));
;         ow[e] = pack2(y0, y1);
;       }
;       *reinterpret_cast<uint4*>(Y + (t0 + t) * YW + g * 128 + c) = make_uint4(ow[0], ow[1], ow[2], ow[3]);
	v_mov_b32_e32 v64, v56
	v_exp_f32_e32 v4, v4
	v_lshlrev_b32_e32 v62, 16, v0
	v_mov_b32_e32 v65, v58
	v_rcp_f32_e32 v61, v61
	s_nop 0
	v_mul_f32_e32 v61, v13, v61
	v_and_b32_e32 v1, 0xffff0000, v1
	v_mul_f32_e32 v5, 0xbfb8aa3b, v21
	v_exp_f32_e32 v5, v5
	v_rcp_f32_e32 v60, v60
	s_nop 0
	v_mul_f32_e32 v60, v17, v60
	v_and_b32_e32 v0, 0xffff0000, v0
	v_mov_b32_e32 v58, v57
	v_pk_add_f32 v[4:5], v[4:5], 1.0 op_sel_hi:[1,0]
	v_pk_mul_f32 v[0:1], v[58:59], v[0:1]
	v_pk_mul_f32 v[62:63], v[64:65], v[62:63]
	v_rcp_f32_e32 v5, v5
	s_nop 0
	v_mul_f32_e32 v5, v21, v5
	v_pk_mul_f32 v[60:61], v[60:61], v[62:63]
	v_rcp_f32_e32 v4, v4
	s_nop 0
	v_mul_f32_e32 v4, v25, v4
	v_pk_mul_f32 v[0:1], v[4:5], v[0:1]
	v_cvt_pk_bf16_f32 v1, 0, v1
	v_cvt_pk_bf16_f32 v0, 0, v0
	v_cvt_pk_bf16_f32 v5, 0, v60
	v_cvt_pk_bf16_f32 v4, 0, v61
	v_and_b32_e32 v1, 0xffff0000, v1
	v_and_b32_e32 v0, 0xffff0000, v0
	v_lshlrev_b32_e32 v13, 16, v7
	v_lshlrev_b32_e32 v17, 16, v6
	v_or_b32_sdwa v1, v1, v4 dst_sel:DWORD dst_unused:UNUSED_PAD src0_sel:DWORD src1_sel:WORD_1
	v_or_b32_sdwa v0, v0, v5 dst_sel:DWORD dst_unused:UNUSED_PAD src0_sel:DWORD src1_sel:WORD_1
	v_mul_f32_e32 v4, 0xbfb8aa3b, v17
	v_mul_f32_e32 v5, 0xbfb8aa3b, v13
	v_exp_f32_e32 v4, v4
	v_exp_f32_e32 v5, v5
	v_and_b32_e32 v25, 0xffff0000, v6
	v_mul_f32_e32 v6, 0xbfb8aa3b, v25
	v_and_b32_e32 v21, 0xffff0000, v7
	v_exp_f32_e32 v60, v6
	v_pk_add_f32 v[64:65], v[4:5], 1.0 op_sel_hi:[1,0]
	global_load_dwordx4 v[4:7], v[14:15], off
	global_load_dwordx4 v[56:59], v[14:15], off offset:2048
	s_waitcnt lgkmcnt(0)
	v_mov_b32_e32 v14, v8
	v_mov_b32_e32 v15, v10
	v_lshlrev_b32_e32 v63, 16, v3
	v_lshlrev_b32_e32 v62, 16, v2
	v_pk_mul_f32 v[14:15], v[14:15], v[62:63]
	v_rcp_f32_e32 v63, v65
	s_nop 0
	v_mul_f32_e32 v63, v13, v63
	v_mul_f32_e32 v10, 0xbfb8aa3b, v21
	v_exp_f32_e32 v61, v10
	v_rcp_f32_e32 v62, v64
	s_nop 0
	v_mul_f32_e32 v62, v17, v62
	v_mov_b32_e32 v10, v9
	v_and_b32_e32 v3, 0xffff0000, v3
	v_pk_add_f32 v[60:61], v[60:61], 1.0 op_sel_hi:[1,0]
	v_and_b32_e32 v2, 0xffff0000, v2
	v_pk_mul_f32 v[2:3], v[10:11], v[2:3]
	v_pk_mul_f32 v[14:15], v[62:63], v[14:15]
	v_rcp_f32_e32 v9, v61
	s_nop 0
	v_mul_f32_e32 v9, v21, v9
	v_rcp_f32_e32 v8, v60
	s_nop 0
	v_mul_f32_e32 v8, v25, v8
	v_pk_mul_f32 v[2:3], v[8:9], v[2:3]
	v_cvt_pk_bf16_f32 v3, 0, v3
	v_cvt_pk_bf16_f32 v8, 0, v15
	v_and_b32_e32 v3, 0xffff0000, v3
	v_or_b32_sdwa v3, v3, v8 dst_sel:DWORD dst_unused:UNUSED_PAD src0_sel:DWORD src1_sel:WORD_1
	v_cvt_pk_bf16_f32 v2, 0, v2
	v_cvt_pk_bf16_f32 v9, 0, v14
	v_and_b32_e32 v2, 0xffff0000, v2
	v_or_b32_sdwa v2, v2, v9 dst_sel:DWORD dst_unused:UNUSED_PAD src0_sel:DWORD src1_sel:WORD_1
	s_waitcnt vmcnt(0)
	v_lshlrev_b32_e32 v21, 16, v56
	v_mul_f32_e32 v8, 0xbfb8aa3b, v21
	v_and_b32_e32 v29, 0xffff0000, v56
	v_lshlrev_b32_e32 v17, 16, v57
	v_exp_f32_e32 v60, v8
	v_mul_f32_e32 v8, 0xbfb8aa3b, v29
	v_exp_f32_e32 v56, v8
	v_mul_f32_e32 v8, 0xbfb8aa3b, v17
	v_exp_f32_e32 v61, v8
	ds_read_b128 v[8:11], v12
	ds_read_b128 v[12:15], v12 offset:16
	v_and_b32_e32 v25, 0xffff0000, v57
	v_lshlrev_b32_e32 v63, 16, v5
	v_pk_add_f32 v[60:61], v[60:61], 1.0 op_sel_hi:[1,0]
	s_waitcnt lgkmcnt(1)
	v_mov_b32_e32 v64, v8
	v_mov_b32_e32 v65, v10
	v_lshlrev_b32_e32 v62, 16, v4
	v_and_b32_e32 v5, 0xffff0000, v5
	v_rcp_f32_e32 v61, v61
	s_nop 0
	v_mul_f32_e32 v61, v17, v61
	v_and_b32_e32 v4, 0xffff0000, v4
	v_mul_f32_e32 v10, 0xbfb8aa3b, v25
	v_exp_f32_e32 v57, v10
	v_rcp_f32_e32 v60, v60
	s_nop 0
	v_mul_f32_e32 v60, v21, v60
	v_mov_b32_e32 v10, v9
	v_pk_mul_f32 v[4:5], v[10:11], v[4:5]
	v_pk_add_f32 v[56:57], v[56:57], 1.0 op_sel_hi:[1,0]
	v_pk_mul_f32 v[62:63], v[64:65], v[62:63]
	v_pk_mul_f32 v[60:61], v[60:61], v[62:63]
	v_lshlrev_b32_e32 v63, 16, v7
	v_lshlrev_b32_e32 v62, 16, v6
	v_rcp_f32_e32 v9, v57
	s_nop 0
	v_mul_f32_e32 v9, v25, v9
	v_rcp_f32_e32 v8, v56
	s_nop 0
	v_mul_f32_e32 v8, v29, v8
	v_pk_mul_f32 v[4:5], v[8:9], v[4:5]
	v_cvt_pk_bf16_f32 v5, 0, v5
	v_cvt_pk_bf16_f32 v4, 0, v4
	v_cvt_pk_bf16_f32 v9, 0, v60
	v_cvt_pk_bf16_f32 v8, 0, v61
	v_and_b32_e32 v5, 0xffff0000, v5
	v_and_b32_e32 v4, 0xffff0000, v4
	v_lshlrev_b32_e32 v17, 16, v59
	v_lshlrev_b32_e32 v21, 16, v58
	v_or_b32_sdwa v5, v5, v8 dst_sel:DWORD dst_unused:UNUSED_PAD src0_sel:DWORD src1_sel:WORD_1
	v_or_b32_sdwa v4, v4, v9 dst_sel:DWORD dst_unused:UNUSED_PAD src0_sel:DWORD src1_sel:WORD_1
	v_mul_f32_e32 v8, 0xbfb8aa3b, v21
	v_mul_f32_e32 v9, 0xbfb8aa3b, v17
	v_exp_f32_e32 v8, v8
	v_exp_f32_e32 v9, v9
	v_and_b32_e32 v29, 0xffff0000, v58
	v_mul_f32_e32 v10, 0xbfb8aa3b, v29
	v_and_b32_e32 v25, 0xffff0000, v59
	v_exp_f32_e32 v60, v10
	v_pk_add_f32 v[64:65], v[8:9], 1.0 op_sel_hi:[1,0]
	global_load_dwordx4 v[8:11], v[18:19], off
	global_load_dwordx4 v[56:59], v[18:19], off offset:2048
	s_waitcnt lgkmcnt(0)
	v_mov_b32_e32 v18, v12
	v_mov_b32_e32 v19, v14
	v_pk_mul_f32 v[18:19], v[18:19], v[62:63]
	v_rcp_f32_e32 v63, v65
	s_nop 0
	v_mul_f32_e32 v63, v17, v63
	v_and_b32_e32 v7, 0xffff0000, v7
	v_mul_f32_e32 v14, 0xbfb8aa3b, v25
	v_exp_f32_e32 v61, v14
	v_rcp_f32_e32 v62, v64
	s_nop 0
	v_mul_f32_e32 v62, v21, v62
	v_mov_b32_e32 v14, v13
	v_and_b32_e32 v6, 0xffff0000, v6
	v_pk_add_f32 v[60:61], v[60:61], 1.0 op_sel_hi:[1,0]
	v_pk_mul_f32 v[6:7], v[14:15], v[6:7]
	v_pk_mul_f32 v[18:19], v[62:63], v[18:19]
	v_rcp_f32_e32 v13, v61
	s_nop 0
	v_mul_f32_e32 v13, v25, v13
	v_rcp_f32_e32 v12, v60
	s_nop 0
	v_mul_f32_e32 v12, v29, v12
	v_pk_mul_f32 v[6:7], v[12:13], v[6:7]
	v_cvt_pk_bf16_f32 v7, 0, v7
	v_cvt_pk_bf16_f32 v12, 0, v19
	v_and_b32_e32 v7, 0xffff0000, v7
	v_or_b32_sdwa v7, v7, v12 dst_sel:DWORD dst_unused:UNUSED_PAD src0_sel:DWORD src1_sel:WORD_1
	v_cvt_pk_bf16_f32 v6, 0, v6
	v_cvt_pk_bf16_f32 v13, 0, v18
	v_and_b32_e32 v6, 0xffff0000, v6
	v_or_b32_sdwa v6, v6, v13 dst_sel:DWORD dst_unused:UNUSED_PAD src0_sel:DWORD src1_sel:WORD_1
	s_waitcnt vmcnt(1)
; __device__ __forceinline__ unsigned pack2(float a, float b) { return (unsigned)f2bf(a) | ((unsigned)f2bf(b) << 16); }
; __device__ __forceinline__ float bflo(unsigned w) { return __uint_as_float(w << 16); }
; __device__ __forceinline__ float bfhi(unsigned w) { return __uint_as_float(w & 0xffff0000u); }
; __device__ __forceinline__ float silu_f(float g) { return g / (1.f + __expf(-g)); }
; __device__ void gmlp_item(const Params& p, int layer, int b, int n, int g, char* smem) {
;     ...
; #pragma unroll
;     for (int i = 0; i < 8; ++i) {
;       int q = tid + 256 * i, t = q >> 4, c = (q & 15) * 8;
;       float4 m0 = *reinterpret_cast<const float4*>(Tf + t * 132 + c);
;       float4 m1 = *reinterpret_cast<const float4*>(Tf + t * 132 + c + 4);
;       float mm[8] = {m0.x, m0.y, m0.z, m0.w, m1.x, m1.y, m1.z, m1.w};
;       unsigned uw[4] = {uu[i].x, uu[i].y, uu[i].z, uu[i].w};
;       unsigned gw[4] = {gt[i].x, gt[i].y, gt[i].z, gt[i].w};
;       unsigned ow[4];
; #pragma unroll
;       for (int e = 0; e < 4; ++e) {
;         float y0 = bflo(uw[e]) * mm[2 * e] * silu_f(bflo(gw[e]));
;         float y1 = bfhi(uw[e]) * mm[2 * e + 1] * silu_f(bfhi(gw[e]));
;         ow[e] = pack2(y0, y1);
;       }
;       *reinterpret_cast<uint4*>(Y + (t0 + t) * YW + g * 128 + c) = make_uint4(ow[0], ow[1], ow[2], ow[3]);
	v_lshlrev_b32_e32 v63, 16, v9
	s_waitcnt vmcnt(0)
	v_lshlrev_b32_e32 v25, 16, v56
	v_mul_f32_e32 v12, 0xbfb8aa3b, v25
	v_and_b32_e32 v35, 0xffff0000, v56
	v_lshlrev_b32_e32 v21, 16, v57
	v_exp_f32_e32 v60, v12
	v_mul_f32_e32 v12, 0xbfb8aa3b, v35
	v_exp_f32_e32 v56, v12
	v_mul_f32_e32 v12, 0xbfb8aa3b, v21
	v_exp_f32_e32 v61, v12
	v_and_b32_e32 v29, 0xffff0000, v57
	ds_read_b128 v[12:15], v16
	ds_read_b128 v[16:19], v16 offset:16
	v_lshlrev_b32_e32 v62, 16, v8
	v_pk_add_f32 v[60:61], v[60:61], 1.0 op_sel_hi:[1,0]
	v_and_b32_e32 v9, 0xffff0000, v9
	s_waitcnt lgkmcnt(1)
	v_mov_b32_e32 v64, v12
	v_mov_b32_e32 v65, v14
	v_pk_mul_f32 v[62:63], v[64:65], v[62:63]
	v_rcp_f32_e32 v61, v61
	s_nop 0
	v_mul_f32_e32 v61, v21, v61
	v_and_b32_e32 v8, 0xffff0000, v8
	v_mul_f32_e32 v14, 0xbfb8aa3b, v29
	v_exp_f32_e32 v57, v14
	v_rcp_f32_e32 v60, v60
	s_nop 0
	v_mul_f32_e32 v60, v25, v60
	v_mov_b32_e32 v14, v13
	v_pk_mul_f32 v[8:9], v[14:15], v[8:9]
	v_pk_add_f32 v[56:57], v[56:57], 1.0 op_sel_hi:[1,0]
	v_pk_mul_f32 v[60:61], v[60:61], v[62:63]
	v_lshlrev_b32_e32 v63, 16, v11
	v_lshlrev_b32_e32 v62, 16, v10
	v_and_b32_e32 v11, 0xffff0000, v11
	v_rcp_f32_e32 v13, v57
	s_nop 0
	v_mul_f32_e32 v13, v29, v13
	v_rcp_f32_e32 v12, v56
	s_nop 0
	v_mul_f32_e32 v12, v35, v12
	v_pk_mul_f32 v[8:9], v[12:13], v[8:9]
	v_cvt_pk_bf16_f32 v9, 0, v9
	v_cvt_pk_bf16_f32 v8, 0, v8
	v_cvt_pk_bf16_f32 v13, 0, v60
	v_cvt_pk_bf16_f32 v12, 0, v61
	v_and_b32_e32 v9, 0xffff0000, v9
	v_and_b32_e32 v8, 0xffff0000, v8
	v_lshlrev_b32_e32 v21, 16, v59
	v_lshlrev_b32_e32 v25, 16, v58
	v_or_b32_sdwa v9, v9, v12 dst_sel:DWORD dst_unused:UNUSED_PAD src0_sel:DWORD src1_sel:WORD_1
	v_or_b32_sdwa v8, v8, v13 dst_sel:DWORD dst_unused:UNUSED_PAD src0_sel:DWORD src1_sel:WORD_1
	v_mul_f32_e32 v12, 0xbfb8aa3b, v25
	v_mul_f32_e32 v13, 0xbfb8aa3b, v21
	v_exp_f32_e32 v12, v12
	v_exp_f32_e32 v13, v13
	v_and_b32_e32 v35, 0xffff0000, v58
	v_mul_f32_e32 v14, 0xbfb8aa3b, v35
	v_and_b32_e32 v29, 0xffff0000, v59
	v_exp_f32_e32 v60, v14
	v_pk_add_f32 v[64:65], v[12:13], 1.0 op_sel_hi:[1,0]
	global_load_dwordx4 v[12:15], v[22:23], off
	global_load_dwordx4 v[56:59], v[22:23], off offset:2048
	s_waitcnt lgkmcnt(0)
	v_mov_b32_e32 v22, v16
	v_mov_b32_e32 v23, v18
	v_pk_mul_f32 v[22:23], v[22:23], v[62:63]
	v_rcp_f32_e32 v63, v65
	s_nop 0
	v_mul_f32_e32 v63, v21, v63
	v_and_b32_e32 v10, 0xffff0000, v10
	v_mul_f32_e32 v18, 0xbfb8aa3b, v29
	v_exp_f32_e32 v61, v18
	v_rcp_f32_e32 v62, v64
	s_nop 0
	v_mul_f32_e32 v62, v25, v62
	v_mov_b32_e32 v18, v17
	v_pk_mul_f32 v[10:11], v[18:19], v[10:11]
	v_pk_add_f32 v[60:61], v[60:61], 1.0 op_sel_hi:[1,0]
	v_pk_mul_f32 v[22:23], v[62:63], v[22:23]
	s_waitcnt vmcnt(1)
	v_lshlrev_b32_e32 v63, 16, v13
	v_rcp_f32_e32 v17, v61
	s_nop 0
	v_mul_f32_e32 v17, v29, v17
	v_rcp_f32_e32 v16, v60
	s_nop 0
	v_mul_f32_e32 v16, v35, v16
	v_pk_mul_f32 v[10:11], v[16:17], v[10:11]
	v_cvt_pk_bf16_f32 v11, 0, v11
	v_cvt_pk_bf16_f32 v16, 0, v23
	v_and_b32_e32 v11, 0xffff0000, v11
	s_waitcnt vmcnt(0)
	v_lshlrev_b32_e32 v29, 16, v56
	v_or_b32_sdwa v11, v11, v16 dst_sel:DWORD dst_unused:UNUSED_PAD src0_sel:DWORD src1_sel:WORD_1
	v_mul_f32_e32 v16, 0xbfb8aa3b, v29
	v_and_b32_e32 v55, 0xffff0000, v56
	v_lshlrev_b32_e32 v25, 16, v57
	v_exp_f32_e32 v60, v16
	v_mul_f32_e32 v16, 0xbfb8aa3b, v55
	v_exp_f32_e32 v56, v16
	v_mul_f32_e32 v16, 0xbfb8aa3b, v25
	v_exp_f32_e32 v61, v16
	v_cvt_pk_bf16_f32 v10, 0, v10
	v_pk_add_f32 v[60:61], v[60:61], 1.0 op_sel_hi:[1,0]
	v_cvt_pk_bf16_f32 v17, 0, v22
	v_and_b32_e32 v10, 0xffff0000, v10
	v_and_b32_e32 v35, 0xffff0000, v57
	v_or_b32_sdwa v10, v10, v17 dst_sel:DWORD dst_unused:UNUSED_PAD src0_sel:DWORD src1_sel:WORD_1
	ds_read_b128 v[16:19], v20
	ds_read_b128 v[20:23], v20 offset:16
	v_lshlrev_b32_e32 v62, 16, v12
	v_and_b32_e32 v13, 0xffff0000, v13
	s_waitcnt lgkmcnt(1)
	v_mov_b32_e32 v64, v16
	v_mov_b32_e32 v65, v18
	v_pk_mul_f32 v[62:63], v[64:65], v[62:63]
	v_rcp_f32_e32 v61, v61
	s_nop 0
	v_mul_f32_e32 v61, v25, v61
	v_and_b32_e32 v12, 0xffff0000, v12
	v_mul_f32_e32 v18, 0xbfb8aa3b, v35
	v_exp_f32_e32 v57, v18
	v_rcp_f32_e32 v60, v60
	s_nop 0
	v_mul_f32_e32 v60, v29, v60
	v_mov_b32_e32 v18, v17
	v_pk_mul_f32 v[12:13], v[18:19], v[12:13]
	v_pk_add_f32 v[56:57], v[56:57], 1.0 op_sel_hi:[1,0]
	v_pk_mul_f32 v[60:61], v[60:61], v[62:63]
	v_lshlrev_b32_e32 v63, 16, v15
	v_lshlrev_b32_e32 v62, 16, v14
	v_and_b32_e32 v15, 0xffff0000, v15
	v_rcp_f32_e32 v17, v57
	s_nop 0
	v_mul_f32_e32 v17, v35, v17
	v_rcp_f32_e32 v16, v56
	s_nop 0
	v_mul_f32_e32 v16, v55, v16
	v_pk_mul_f32 v[12:13], v[16:17], v[12:13]
	v_cvt_pk_bf16_f32 v13, 0, v13
	v_cvt_pk_bf16_f32 v12, 0, v12
	v_cvt_pk_bf16_f32 v17, 0, v60
	v_cvt_pk_bf16_f32 v16, 0, v61
	v_and_b32_e32 v13, 0xffff0000, v13
	v_and_b32_e32 v12, 0xffff0000, v12
	v_lshlrev_b32_e32 v25, 16, v59
	v_lshlrev_b32_e32 v29, 16, v58
	v_or_b32_sdwa v13, v13, v16 dst_sel:DWORD dst_unused:UNUSED_PAD src0_sel:DWORD src1_sel:WORD_1
	v_or_b32_sdwa v12, v12, v17 dst_sel:DWORD dst_unused:UNUSED_PAD src0_sel:DWORD src1_sel:WORD_1
	v_mul_f32_e32 v16, 0xbfb8aa3b, v29
	v_mul_f32_e32 v17, 0xbfb8aa3b, v25
	v_exp_f32_e32 v16, v16
	v_exp_f32_e32 v17, v17
	v_and_b32_e32 v55, 0xffff0000, v58
	v_mul_f32_e32 v18, 0xbfb8aa3b, v55
	v_and_b32_e32 v35, 0xffff0000, v59
	v_exp_f32_e32 v60, v18
	v_pk_add_f32 v[64:65], v[16:17], 1.0 op_sel_hi:[1,0]
	global_load_dwordx4 v[16:19], v[26:27], off
	global_load_dwordx4 v[56:59], v[26:27], off offset:2048
	s_waitcnt lgkmcnt(0)
; __device__ __forceinline__ unsigned pack2(float a, float b) { return (unsigned)f2bf(a) | ((unsigned)f2bf(b) << 16); }
; __device__ __forceinline__ float bflo(unsigned w) { return __uint_as_float(w << 16); }
; __device__ __forceinline__ float bfhi(unsigned w) { return __uint_as_float(w & 0xffff0000u); }
; __device__ __forceinline__ float silu_f(float g) { return g / (1.f + __expf(-g)); }
; __device__ void gmlp_item(const Params& p, int layer, int b, int n, int g, char* smem) {
;     ...
; #pragma unroll
;     for (int i = 0; i < 8; ++i) {
;       int q = tid + 256 * i, t = q >> 4, c = (q & 15) * 8;
;       float4 m0 = *reinterpret_cast<const float4*>(Tf + t * 132 + c);
;       float4 m1 = *reinterpret_cast<const float4*>(Tf + t * 132 + c + 4);
;       float mm[8] = {m0.x, m0.y, m0.z, m0.w, m1.x, m1.y, m1.z, m1.w};
;       unsigned uw[4] = {uu[i].x, uu[i].y, uu[i].z, uu[i].w};
;       unsigned gw[4] = {gt[i].x, gt[i].y, gt[i].z, gt[i].w};
;       unsigned ow[4];
; #pragma unroll
;       for (int e = 0; e < 4; ++e) {
;         float y0 = bflo(uw[e]) * mm[2 * e] * silu_f(bflo(gw[e]));
;         float y1 = bfhi(uw[e]) * mm[2 * e + 1] * silu_f(bfhi(gw[e]));
;         ow[e] = pack2(y0, y1);
;       }
;       *reinterpret_cast<uint4*>(Y + (t0 + t) * YW + g * 128 + c) = make_uint4(ow[0], ow[1], ow[2], ow[3]);
	v_mov_b32_e32 v26, v20
	v_mov_b32_e32 v27, v22
	v_pk_mul_f32 v[26:27], v[26:27], v[62:63]
	v_rcp_f32_e32 v63, v65
	s_nop 0
	v_mul_f32_e32 v63, v25, v63
	v_and_b32_e32 v14, 0xffff0000, v14
	v_mul_f32_e32 v22, 0xbfb8aa3b, v35
	v_exp_f32_e32 v61, v22
	v_rcp_f32_e32 v62, v64
	s_nop 0
	v_mul_f32_e32 v62, v29, v62
	v_mov_b32_e32 v22, v21
	v_pk_mul_f32 v[14:15], v[22:23], v[14:15]
	v_pk_add_f32 v[60:61], v[60:61], 1.0 op_sel_hi:[1,0]
	v_pk_mul_f32 v[26:27], v[62:63], v[26:27]
	s_waitcnt vmcnt(1)
	v_lshlrev_b32_e32 v63, 16, v17
	v_rcp_f32_e32 v21, v61
	s_nop 0
	v_mul_f32_e32 v21, v35, v21
	v_rcp_f32_e32 v20, v60
	s_nop 0
	v_mul_f32_e32 v20, v55, v20
	v_pk_mul_f32 v[14:15], v[20:21], v[14:15]
	v_cvt_pk_bf16_f32 v15, 0, v15
	v_cvt_pk_bf16_f32 v20, 0, v27
	v_and_b32_e32 v15, 0xffff0000, v15
	s_waitcnt vmcnt(0)
	v_lshlrev_b32_e32 v35, 16, v56
	v_or_b32_sdwa v15, v15, v20 dst_sel:DWORD dst_unused:UNUSED_PAD src0_sel:DWORD src1_sel:WORD_1
	v_mul_f32_e32 v20, 0xbfb8aa3b, v35
	v_and_b32_e32 v66, 0xffff0000, v56
	v_lshlrev_b32_e32 v29, 16, v57
	v_exp_f32_e32 v60, v20
	v_mul_f32_e32 v20, 0xbfb8aa3b, v66
	v_exp_f32_e32 v56, v20
	v_mul_f32_e32 v20, 0xbfb8aa3b, v29
	v_exp_f32_e32 v61, v20
	v_cvt_pk_bf16_f32 v14, 0, v14
	v_pk_add_f32 v[60:61], v[60:61], 1.0 op_sel_hi:[1,0]
	v_cvt_pk_bf16_f32 v21, 0, v26
	v_and_b32_e32 v14, 0xffff0000, v14
	v_and_b32_e32 v55, 0xffff0000, v57
	v_or_b32_sdwa v14, v14, v21 dst_sel:DWORD dst_unused:UNUSED_PAD src0_sel:DWORD src1_sel:WORD_1
	ds_read_b128 v[20:23], v24
	ds_read_b128 v[24:27], v24 offset:16
	v_lshlrev_b32_e32 v62, 16, v16
	v_and_b32_e32 v17, 0xffff0000, v17
	s_waitcnt lgkmcnt(1)
	v_mov_b32_e32 v64, v20
	v_mov_b32_e32 v65, v22
	v_pk_mul_f32 v[62:63], v[64:65], v[62:63]
	v_rcp_f32_e32 v61, v61
	s_nop 0
	v_mul_f32_e32 v61, v29, v61
	v_and_b32_e32 v16, 0xffff0000, v16
	v_mul_f32_e32 v22, 0xbfb8aa3b, v55
	v_exp_f32_e32 v57, v22
	v_rcp_f32_e32 v60, v60
	s_nop 0
	v_mul_f32_e32 v60, v35, v60
	v_mov_b32_e32 v22, v21
	v_pk_mul_f32 v[16:17], v[22:23], v[16:17]
	v_pk_add_f32 v[56:57], v[56:57], 1.0 op_sel_hi:[1,0]
	v_pk_mul_f32 v[60:61], v[60:61], v[62:63]
	v_lshlrev_b32_e32 v63, 16, v19
	v_lshlrev_b32_e32 v62, 16, v18
	v_and_b32_e32 v19, 0xffff0000, v19
	v_rcp_f32_e32 v21, v57
	s_nop 0
	v_mul_f32_e32 v21, v55, v21
	v_rcp_f32_e32 v20, v56
	s_nop 0
	v_mul_f32_e32 v20, v66, v20
	v_pk_mul_f32 v[16:17], v[20:21], v[16:17]
	v_cvt_pk_bf16_f32 v17, 0, v17
	v_cvt_pk_bf16_f32 v16, 0, v16
	v_cvt_pk_bf16_f32 v21, 0, v60
	v_cvt_pk_bf16_f32 v20, 0, v61
	v_and_b32_e32 v17, 0xffff0000, v17
	v_and_b32_e32 v16, 0xffff0000, v16
	v_lshlrev_b32_e32 v29, 16, v59
	v_lshlrev_b32_e32 v35, 16, v58
	v_or_b32_sdwa v17, v17, v20 dst_sel:DWORD dst_unused:UNUSED_PAD src0_sel:DWORD src1_sel:WORD_1
	v_or_b32_sdwa v16, v16, v21 dst_sel:DWORD dst_unused:UNUSED_PAD src0_sel:DWORD src1_sel:WORD_1
	v_mul_f32_e32 v20, 0xbfb8aa3b, v35
	v_mul_f32_e32 v21, 0xbfb8aa3b, v29
	v_exp_f32_e32 v20, v20
	v_exp_f32_e32 v21, v21
	v_and_b32_e32 v66, 0xffff0000, v58
	v_mul_f32_e32 v22, 0xbfb8aa3b, v66
	v_and_b32_e32 v55, 0xffff0000, v59
	v_exp_f32_e32 v60, v22
	v_pk_add_f32 v[64:65], v[20:21], 1.0 op_sel_hi:[1,0]
	global_load_dwordx4 v[20:23], v[30:31], off
	global_load_dwordx4 v[56:59], v[30:31], off offset:2048
	s_waitcnt lgkmcnt(0)
	v_mov_b32_e32 v30, v24
	v_mov_b32_e32 v31, v26
	v_pk_mul_f32 v[30:31], v[30:31], v[62:63]
	v_rcp_f32_e32 v63, v65
	s_nop 0
	v_mul_f32_e32 v63, v29, v63
	v_and_b32_e32 v18, 0xffff0000, v18
	v_mul_f32_e32 v26, 0xbfb8aa3b, v55
	v_exp_f32_e32 v61, v26
	v_rcp_f32_e32 v62, v64
	s_nop 0
	v_mul_f32_e32 v62, v35, v62
	v_mov_b32_e32 v26, v25
	v_pk_mul_f32 v[18:19], v[26:27], v[18:19]
	v_pk_add_f32 v[60:61], v[60:61], 1.0 op_sel_hi:[1,0]
	v_pk_mul_f32 v[30:31], v[62:63], v[30:31]
	s_waitcnt vmcnt(1)
	v_lshlrev_b32_e32 v63, 16, v21
	v_rcp_f32_e32 v25, v61
	s_nop 0
	v_mul_f32_e32 v25, v55, v25
	v_rcp_f32_e32 v24, v60
	s_nop 0
	v_mul_f32_e32 v24, v66, v24
	v_pk_mul_f32 v[18:19], v[24:25], v[18:19]
	v_cvt_pk_bf16_f32 v19, 0, v19
	v_cvt_pk_bf16_f32 v24, 0, v31
	v_and_b32_e32 v19, 0xffff0000, v19
	s_waitcnt vmcnt(0)
	v_lshlrev_b32_e32 v55, 16, v56
	v_or_b32_sdwa v19, v19, v24 dst_sel:DWORD dst_unused:UNUSED_PAD src0_sel:DWORD src1_sel:WORD_1
	v_mul_f32_e32 v24, 0xbfb8aa3b, v55
	v_and_b32_e32 v67, 0xffff0000, v56
	v_lshlrev_b32_e32 v35, 16, v57
	v_exp_f32_e32 v60, v24
	v_mul_f32_e32 v24, 0xbfb8aa3b, v67
	v_exp_f32_e32 v56, v24
	v_mul_f32_e32 v24, 0xbfb8aa3b, v35
	v_exp_f32_e32 v61, v24
	v_cvt_pk_bf16_f32 v18, 0, v18
	v_pk_add_f32 v[60:61], v[60:61], 1.0 op_sel_hi:[1,0]
	v_cvt_pk_bf16_f32 v25, 0, v30
	v_and_b32_e32 v18, 0xffff0000, v18
	v_and_b32_e32 v66, 0xffff0000, v57
	v_or_b32_sdwa v18, v18, v25 dst_sel:DWORD dst_unused:UNUSED_PAD src0_sel:DWORD src1_sel:WORD_1
	ds_read_b128 v[24:27], v28
	ds_read_b128 v[28:31], v28 offset:16
	v_lshlrev_b32_e32 v62, 16, v20
	v_and_b32_e32 v21, 0xffff0000, v21
	s_waitcnt lgkmcnt(1)
; __device__ __forceinline__ unsigned pack2(float a, float b) { return (unsigned)f2bf(a) | ((unsigned)f2bf(b) << 16); }
; __device__ __forceinline__ float bflo(unsigned w) { return __uint_as_float(w << 16); }
; __device__ __forceinline__ float bfhi(unsigned w) { return __uint_as_float(w & 0xffff0000u); }
; __device__ __forceinline__ float silu_f(float g) { return g / (1.f + __expf(-g)); }
; __device__ void gmlp_item(const Params& p, int layer, int b, int n, int g, char* smem) {
;     ...
; #pragma unroll
;     for (int i = 0; i < 8; ++i) {
;       int q = tid + 256 * i, t = q >> 4, c = (q & 15) * 8;
;       float4 m0 = *reinterpret_cast<const float4*>(Tf + t * 132 + c);
;       float4 m1 = *reinterpret_cast<const float4*>(Tf + t * 132 + c + 4);
;       float mm[8] = {m0.x, m0.y, m0.z, m0.w, m1.x, m1.y, m1.z, m1.w};
;       unsigned uw[4] = {uu[i].x, uu[i].y, uu[i].z, uu[i].w};
;       unsigned gw[4] = {gt[i].x, gt[i].y, gt[i].z, gt[i].w};
;       unsigned ow[4];
; #pragma unroll
;       for (int e = 0; e < 4; ++e) {
;         float y0 = bflo(uw[e]) * mm[2 * e] * silu_f(bflo(gw[e]));
;         float y1 = bfhi(uw[e]) * mm[2 * e + 1] * silu_f(bfhi(gw[e]));
;         ow[e] = pack2(y0, y1);
;       }
;       *reinterpret_cast<uint4*>(Y + (t0 + t) * YW + g * 128 + c) = make_uint4(ow[0], ow[1], ow[2], ow[3]);
	v_mov_b32_e32 v64, v24
	v_mov_b32_e32 v65, v26
	v_pk_mul_f32 v[62:63], v[64:65], v[62:63]
	v_rcp_f32_e32 v61, v61
	s_nop 0
	v_mul_f32_e32 v61, v35, v61
	v_and_b32_e32 v20, 0xffff0000, v20
	v_mul_f32_e32 v26, 0xbfb8aa3b, v66
	v_exp_f32_e32 v57, v26
	v_rcp_f32_e32 v60, v60
	s_nop 0
	v_mul_f32_e32 v60, v55, v60
	v_mov_b32_e32 v26, v25
	v_pk_mul_f32 v[20:21], v[26:27], v[20:21]
	v_pk_add_f32 v[56:57], v[56:57], 1.0 op_sel_hi:[1,0]
	v_pk_mul_f32 v[60:61], v[60:61], v[62:63]
	v_lshlrev_b32_e32 v63, 16, v23
	v_lshlrev_b32_e32 v62, 16, v22
	v_and_b32_e32 v23, 0xffff0000, v23
	v_rcp_f32_e32 v25, v57
	s_nop 0
	v_mul_f32_e32 v25, v66, v25
	v_rcp_f32_e32 v24, v56
	s_nop 0
	v_mul_f32_e32 v24, v67, v24
	v_pk_mul_f32 v[20:21], v[24:25], v[20:21]
	v_cvt_pk_bf16_f32 v21, 0, v21
	v_cvt_pk_bf16_f32 v20, 0, v20
	v_cvt_pk_bf16_f32 v25, 0, v60
	v_cvt_pk_bf16_f32 v24, 0, v61
	v_and_b32_e32 v21, 0xffff0000, v21
	v_and_b32_e32 v20, 0xffff0000, v20
	v_lshlrev_b32_e32 v35, 16, v59
	v_lshlrev_b32_e32 v55, 16, v58
	v_or_b32_sdwa v21, v21, v24 dst_sel:DWORD dst_unused:UNUSED_PAD src0_sel:DWORD src1_sel:WORD_1
	v_or_b32_sdwa v20, v20, v25 dst_sel:DWORD dst_unused:UNUSED_PAD src0_sel:DWORD src1_sel:WORD_1
	v_mul_f32_e32 v24, 0xbfb8aa3b, v55
	v_mul_f32_e32 v25, 0xbfb8aa3b, v35
	v_exp_f32_e32 v24, v24
	v_exp_f32_e32 v25, v25
	v_and_b32_e32 v67, 0xffff0000, v58
	v_mul_f32_e32 v26, 0xbfb8aa3b, v67
	v_and_b32_e32 v66, 0xffff0000, v59
	v_exp_f32_e32 v60, v26
	v_pk_add_f32 v[64:65], v[24:25], 1.0 op_sel_hi:[1,0]
	global_load_dwordx4 v[24:27], v[32:33], off
	global_load_dwordx4 v[56:59], v[32:33], off offset:2048
	s_waitcnt lgkmcnt(0)
	v_mov_b32_e32 v32, v28
	v_mov_b32_e32 v33, v30
	v_pk_mul_f32 v[32:33], v[32:33], v[62:63]
	v_rcp_f32_e32 v63, v65
	s_nop 0
	v_mul_f32_e32 v63, v35, v63
	v_and_b32_e32 v22, 0xffff0000, v22
	v_mul_f32_e32 v30, 0xbfb8aa3b, v66
	v_exp_f32_e32 v61, v30
	v_rcp_f32_e32 v62, v64
	s_nop 0
	v_mul_f32_e32 v62, v55, v62
	v_mov_b32_e32 v30, v29
	v_pk_mul_f32 v[22:23], v[30:31], v[22:23]
	v_pk_add_f32 v[60:61], v[60:61], 1.0 op_sel_hi:[1,0]
	v_pk_mul_f32 v[32:33], v[62:63], v[32:33]
	s_waitcnt vmcnt(1)
	v_lshlrev_b32_e32 v63, 16, v25
	v_rcp_f32_e32 v29, v61
	s_nop 0
	v_mul_f32_e32 v29, v66, v29
	v_rcp_f32_e32 v28, v60
	s_nop 0
	v_mul_f32_e32 v28, v67, v28
	v_pk_mul_f32 v[22:23], v[28:29], v[22:23]
	v_cvt_pk_bf16_f32 v23, 0, v23
	v_cvt_pk_bf16_f32 v28, 0, v33
	v_and_b32_e32 v23, 0xffff0000, v23
	s_waitcnt vmcnt(0)
	v_lshlrev_b32_e32 v66, 16, v56
	v_or_b32_sdwa v23, v23, v28 dst_sel:DWORD dst_unused:UNUSED_PAD src0_sel:DWORD src1_sel:WORD_1
	v_mul_f32_e32 v28, 0xbfb8aa3b, v66
	v_and_b32_e32 v68, 0xffff0000, v56
	v_lshlrev_b32_e32 v55, 16, v57
	v_exp_f32_e32 v60, v28
	v_mul_f32_e32 v28, 0xbfb8aa3b, v68
	v_exp_f32_e32 v56, v28
	v_mul_f32_e32 v28, 0xbfb8aa3b, v55
	v_exp_f32_e32 v61, v28
	v_cvt_pk_bf16_f32 v22, 0, v22
	v_pk_add_f32 v[60:61], v[60:61], 1.0 op_sel_hi:[1,0]
	v_cvt_pk_bf16_f32 v29, 0, v32
	v_and_b32_e32 v22, 0xffff0000, v22
	v_and_b32_e32 v67, 0xffff0000, v57
	v_or_b32_sdwa v22, v22, v29 dst_sel:DWORD dst_unused:UNUSED_PAD src0_sel:DWORD src1_sel:WORD_1
	ds_read_b128 v[28:31], v34
	ds_read_b128 v[32:35], v34 offset:16
	v_lshlrev_b32_e32 v62, 16, v24
	v_and_b32_e32 v25, 0xffff0000, v25
	s_waitcnt lgkmcnt(1)
	v_mov_b32_e32 v64, v28
	v_mov_b32_e32 v65, v30
	v_pk_mul_f32 v[62:63], v[64:65], v[62:63]
	v_rcp_f32_e32 v61, v61
	s_nop 0
	v_mul_f32_e32 v61, v55, v61
	v_and_b32_e32 v24, 0xffff0000, v24
	v_mul_f32_e32 v30, 0xbfb8aa3b, v67
	v_exp_f32_e32 v57, v30
	v_rcp_f32_e32 v60, v60
	s_nop 0
	v_mul_f32_e32 v60, v66, v60
	v_mov_b32_e32 v30, v29
	v_pk_mul_f32 v[24:25], v[30:31], v[24:25]
	v_pk_add_f32 v[56:57], v[56:57], 1.0 op_sel_hi:[1,0]
	v_pk_mul_f32 v[60:61], v[60:61], v[62:63]
	v_lshlrev_b32_e32 v66, 16, v58
	v_lshlrev_b32_e32 v63, 16, v27
	v_and_b32_e32 v27, 0xffff0000, v27
	v_rcp_f32_e32 v29, v57
	s_nop 0
	v_mul_f32_e32 v29, v67, v29
	v_rcp_f32_e32 v28, v56
	s_nop 0
	v_mul_f32_e32 v28, v68, v28
	v_pk_mul_f32 v[24:25], v[28:29], v[24:25]
	v_cvt_pk_bf16_f32 v25, 0, v25
	v_cvt_pk_bf16_f32 v24, 0, v24
	v_cvt_pk_bf16_f32 v29, 0, v60
	v_cvt_pk_bf16_f32 v28, 0, v61
	v_and_b32_e32 v25, 0xffff0000, v25
	v_and_b32_e32 v24, 0xffff0000, v24
	v_lshlrev_b32_e32 v55, 16, v59
	v_or_b32_sdwa v25, v25, v28 dst_sel:DWORD dst_unused:UNUSED_PAD src0_sel:DWORD src1_sel:WORD_1
	v_or_b32_sdwa v24, v24, v29 dst_sel:DWORD dst_unused:UNUSED_PAD src0_sel:DWORD src1_sel:WORD_1
	v_mul_f32_e32 v28, 0xbfb8aa3b, v66
	v_mul_f32_e32 v29, 0xbfb8aa3b, v55
	v_exp_f32_e32 v28, v28
	v_exp_f32_e32 v29, v29
	v_and_b32_e32 v68, 0xffff0000, v58
	v_mul_f32_e32 v30, 0xbfb8aa3b, v68
	v_and_b32_e32 v67, 0xffff0000, v59
	v_exp_f32_e32 v60, v30
	v_pk_add_f32 v[64:65], v[28:29], 1.0 op_sel_hi:[1,0]
	global_load_dwordx4 v[28:31], v[52:53], off
	global_load_dwordx4 v[56:59], v[52:53], off offset:2048
	s_waitcnt lgkmcnt(0)
; __device__ __forceinline__ unsigned pack2(float a, float b) { return (unsigned)f2bf(a) | ((unsigned)f2bf(b) << 16); }
; __device__ __forceinline__ float bflo(unsigned w) { return __uint_as_float(w << 16); }
; __device__ __forceinline__ float bfhi(unsigned w) { return __uint_as_float(w & 0xffff0000u); }
; __device__ __forceinline__ float silu_f(float g) { return g / (1.f + __expf(-g)); }
; __device__ void gmlp_item(const Params& p, int layer, int b, int n, int g, char* smem) {
;     ...
; #pragma unroll
;     for (int i = 0; i < 8; ++i) {
;       int q = tid + 256 * i, t = q >> 4, c = (q & 15) * 8;
;       float4 m0 = *reinterpret_cast<const float4*>(Tf + t * 132 + c);
;       float4 m1 = *reinterpret_cast<const float4*>(Tf + t * 132 + c + 4);
;       float mm[8] = {m0.x, m0.y, m0.z, m0.w, m1.x, m1.y, m1.z, m1.w};
;       unsigned uw[4] = {uu[i].x, uu[i].y, uu[i].z, uu[i].w};
;       unsigned gw[4] = {gt[i].x, gt[i].y, gt[i].z, gt[i].w};
;       unsigned ow[4];
; #pragma unroll
;       for (int e = 0; e < 4; ++e) {
;         float y0 = bflo(uw[e]) * mm[2 * e] * silu_f(bflo(gw[e]));
;         float y1 = bfhi(uw[e]) * mm[2 * e + 1] * silu_f(bfhi(gw[e]));
;         ow[e] = pack2(y0, y1);
;       }
;       *reinterpret_cast<uint4*>(Y + (t0 + t) * YW + g * 128 + c) = make_uint4(ow[0], ow[1], ow[2], ow[3]);
;     }
	v_mov_b32_e32 v52, v32
	v_lshlrev_b32_e32 v62, 16, v26
	v_mov_b32_e32 v53, v34
	v_pk_mul_f32 v[52:53], v[52:53], v[62:63]
	v_rcp_f32_e32 v63, v65
	s_nop 0
	v_mul_f32_e32 v63, v55, v63
	v_and_b32_e32 v26, 0xffff0000, v26
	v_mul_f32_e32 v34, 0xbfb8aa3b, v67
	v_exp_f32_e32 v61, v34
	v_rcp_f32_e32 v62, v64
	s_nop 0
	v_mul_f32_e32 v62, v66, v62
	v_mov_b32_e32 v34, v33
	v_pk_mul_f32 v[26:27], v[34:35], v[26:27]
	v_pk_add_f32 v[60:61], v[60:61], 1.0 op_sel_hi:[1,0]
	v_pk_mul_f32 v[52:53], v[62:63], v[52:53]
	s_waitcnt vmcnt(1)
	v_lshlrev_b32_e32 v63, 16, v29
	v_rcp_f32_e32 v33, v61
	s_nop 0
	v_mul_f32_e32 v33, v67, v33
	v_rcp_f32_e32 v32, v60
	s_nop 0
	v_mul_f32_e32 v32, v68, v32
	v_pk_mul_f32 v[26:27], v[32:33], v[26:27]
	v_cvt_pk_bf16_f32 v27, 0, v27
	v_cvt_pk_bf16_f32 v32, 0, v53
	v_and_b32_e32 v27, 0xffff0000, v27
	s_waitcnt vmcnt(0)
	v_lshlrev_b32_e32 v67, 16, v56
	v_or_b32_sdwa v27, v27, v32 dst_sel:DWORD dst_unused:UNUSED_PAD src0_sel:DWORD src1_sel:WORD_1
	v_mul_f32_e32 v32, 0xbfb8aa3b, v67
	v_and_b32_e32 v69, 0xffff0000, v56
	v_lshlrev_b32_e32 v66, 16, v57
	v_exp_f32_e32 v60, v32
	v_mul_f32_e32 v32, 0xbfb8aa3b, v69
	v_exp_f32_e32 v56, v32
	v_mul_f32_e32 v32, 0xbfb8aa3b, v66
	v_exp_f32_e32 v61, v32
	v_cvt_pk_bf16_f32 v26, 0, v26
	v_pk_add_f32 v[60:61], v[60:61], 1.0 op_sel_hi:[1,0]
	v_cvt_pk_bf16_f32 v33, 0, v52
	v_and_b32_e32 v26, 0xffff0000, v26
	v_and_b32_e32 v68, 0xffff0000, v57
	v_or_b32_sdwa v26, v26, v33 dst_sel:DWORD dst_unused:UNUSED_PAD src0_sel:DWORD src1_sel:WORD_1
	ds_read_b128 v[32:35], v54
	ds_read_b128 v[52:55], v54 offset:16
	v_lshlrev_b32_e32 v62, 16, v28
	v_and_b32_e32 v29, 0xffff0000, v29
	s_waitcnt lgkmcnt(1)
	v_mov_b32_e32 v64, v32
	v_mov_b32_e32 v65, v34
	v_pk_mul_f32 v[62:63], v[64:65], v[62:63]
	v_rcp_f32_e32 v61, v61
	s_nop 0
	v_mul_f32_e32 v61, v66, v61
	v_and_b32_e32 v28, 0xffff0000, v28
	v_mul_f32_e32 v34, 0xbfb8aa3b, v68
	v_exp_f32_e32 v57, v34
	v_rcp_f32_e32 v60, v60
	s_nop 0
	v_mul_f32_e32 v60, v67, v60
	v_pk_mul_f32 v[60:61], v[60:61], v[62:63]
	v_mov_b32_e32 v34, v33
	v_pk_add_f32 v[56:57], v[56:57], 1.0 op_sel_hi:[1,0]
	v_pk_mul_f32 v[28:29], v[34:35], v[28:29]
	s_nop 0
	v_rcp_f32_e32 v33, v57
	s_nop 0
	v_mul_f32_e32 v33, v68, v33
	v_rcp_f32_e32 v32, v56
	s_nop 0
	v_mul_f32_e32 v32, v69, v32
	v_pk_mul_f32 v[28:29], v[32:33], v[28:29]
	v_cvt_pk_bf16_f32 v29, 0, v29
	v_cvt_pk_bf16_f32 v28, 0, v28
	v_cvt_pk_bf16_f32 v33, 0, v60
	v_cvt_pk_bf16_f32 v32, 0, v61
	v_and_b32_e32 v29, 0xffff0000, v29
	v_and_b32_e32 v28, 0xffff0000, v28
	v_lshlrev_b32_e32 v35, 16, v59
	v_lshlrev_b32_e32 v60, 16, v58
	v_or_b32_sdwa v29, v29, v32 dst_sel:DWORD dst_unused:UNUSED_PAD src0_sel:DWORD src1_sel:WORD_1
	v_or_b32_sdwa v28, v28, v33 dst_sel:DWORD dst_unused:UNUSED_PAD src0_sel:DWORD src1_sel:WORD_1
	v_mul_f32_e32 v32, 0xbfb8aa3b, v60
	v_mul_f32_e32 v33, 0xbfb8aa3b, v35
	v_exp_f32_e32 v32, v32
	v_exp_f32_e32 v33, v33
	v_and_b32_e32 v62, 0xffff0000, v58
	s_waitcnt lgkmcnt(0)
	v_mov_b32_e32 v58, v52
	v_and_b32_e32 v61, 0xffff0000, v59
	v_pk_add_f32 v[32:33], v[32:33], 1.0 op_sel_hi:[1,0]
	v_lshlrev_b32_e32 v57, 16, v31
	v_lshlrev_b32_e32 v56, 16, v30
	v_mov_b32_e32 v59, v54
	v_pk_mul_f32 v[56:57], v[58:59], v[56:57]
	v_rcp_f32_e32 v33, v33
	s_nop 0
	v_mul_f32_e32 v33, v35, v33
	v_mul_f32_e32 v34, 0xbfb8aa3b, v62
	v_mul_f32_e32 v35, 0xbfb8aa3b, v61
	v_exp_f32_e32 v34, v34
	v_exp_f32_e32 v35, v35
	v_rcp_f32_e32 v32, v32
	s_nop 0
	v_mul_f32_e32 v32, v60, v32
	v_pk_mul_f32 v[32:33], v[32:33], v[56:57]
	v_mov_b32_e32 v54, v53
	v_pk_add_f32 v[34:35], v[34:35], 1.0 op_sel_hi:[1,0]
	v_and_b32_e32 v31, 0xffff0000, v31
	v_and_b32_e32 v30, 0xffff0000, v30
	v_pk_mul_f32 v[30:31], v[54:55], v[30:31]
	v_rcp_f32_e32 v35, v35
	s_nop 0
	v_mul_f32_e32 v35, v61, v35
	s_mov_b64 s[12:13], 0
	v_rcp_f32_e32 v34, v34
	s_nop 0
	v_mul_f32_e32 v34, v62, v34
	v_pk_mul_f32 v[30:31], v[34:35], v[30:31]
	v_cvt_pk_bf16_f32 v32, 0, v32
	v_cvt_pk_bf16_f32 v33, 0, v33
	v_cvt_pk_bf16_f32 v31, 0, v31
	v_cvt_pk_bf16_f32 v30, 0, v30
	v_and_b32_e32 v31, 0xffff0000, v31
	v_and_b32_e32 v30, 0xffff0000, v30
	v_or_b32_sdwa v31, v31, v33 dst_sel:DWORD dst_unused:UNUSED_PAD src0_sel:DWORD src1_sel:WORD_1
	v_or_b32_sdwa v30, v30, v32 dst_sel:DWORD dst_unused:UNUSED_PAD src0_sel:DWORD src1_sel:WORD_1
	global_store_dwordx4 v[50:51], v[28:31], off
	global_store_dwordx4 v[48:49], v[24:27], off
	global_store_dwordx4 v[46:47], v[20:23], off
	global_store_dwordx4 v[44:45], v[16:19], off
	global_store_dwordx4 v[42:43], v[12:15], off
	global_store_dwordx4 v[40:41], v[8:11], off
	global_store_dwordx4 v[38:39], v[4:7], off
	global_store_dwordx4 v[36:37], v[0:3], off
	s_barrier

; template <int DH, int MODE>
; __device__ void attn_item(const Params& p, int layer, int b, int blk, int head, char* smem) {
;     ...
;     V_SCATTER_(vr0, 0);
;     V_SCATTER_(vr1, 1);
;     if (KCH > 2) {
;       V_SCATTER_(vr2, 2);
;       V_SCATTER_(vr3, 3);
;     }
;     KV_LOAD_(it + 1);
;     if (!wskip) {
;       float4* s4 = reinterpret_cast<float4*>(Sf + row * SSTR + half * 32);
;       char* prow = Pb + half * 8192 + row * 64;
;       if (MODE == 0) {
;         const int kjb = kj0 + half * 32;
;         float tmax = -1e30f;
; #pragma unroll
;         for (int c = 0; c < 8; ++c) {
;           float4 v = s4[c];
;           float e[4] = {v.x, v.y, v.z, v.w};
; #pragma unroll
;           for (int k = 0; k < 4; ++k) {
;             int kj = kjb + c * 4 + k;
;             bool valid = (kj > row) && (kj <= row + 128);
;             tmax = valid ? fmaxf(tmax, e[k]) : tmax;
;           }
;         }
.LBB0_487:
	s_or_b64 exec, exec, s[14:15]
	s_add_i32 s89, s89, 1
	s_min_i32 s14, s89, s87
	s_add_i32 s14, s14, s86
	s_lshl_b32 s14, s14, 6
	s_add_i32 s14, s14, s88
	s_ashr_i32 s15, s14, 31
	s_add_u32 s14, s14, s84
	s_addc_u32 s15, s15, 0
	s_waitcnt lgkmcnt(0)
	s_barrier
	ds_write_b16 v96, v48
	ds_write_b16_d16_hi v96, v48 offset:64
	ds_write_b16 v96, v49 offset:128
	ds_write_b16_d16_hi v96, v49 offset:192
	ds_write_b16 v96, v50 offset:256
	ds_write_b16_d16_hi v96, v50 offset:320
	ds_write_b16 v96, v51 offset:384
	ds_write_b16_d16_hi v96, v51 offset:448
	s_waitcnt vmcnt(0)
	ds_write_b16 v96, v52 offset:2048
	ds_write_b16_d16_hi v96, v52 offset:2112
	ds_write_b16 v96, v53 offset:2176
	ds_write_b16_d16_hi v96, v53 offset:2240
	ds_write_b16 v96, v54 offset:2304
	ds_write_b16_d16_hi v96, v54 offset:2368
	ds_write_b16 v96, v55 offset:2432
	ds_write_b16_d16_hi v96, v55 offset:2496
	v_lshl_add_u64 v[48:49], s[14:15], 0, v[66:67]
	v_mad_u64_u32 v[52:53], s[20:21], v48, s63, v[76:77]
	v_or_b32_e32 v48, s14, v72
	v_mad_i32_i24 v53, v49, s63, v53
	v_mad_u64_u32 v[54:55], s[20:21], v48, s63, v[78:79]
	v_add_co_u32_e32 v48, vcc, 0x4c000, v52
	v_mad_i32_i24 v55, s15, v160, v55
	s_nop 0
	v_addc_co_u32_e32 v49, vcc, 0, v53, vcc
	global_load_dwordx4 v[60:63], v[48:49], off
	s_nop 0
	global_load_dwordx4 v[48:51], v[54:55], off
	global_load_dwordx4 v[56:59], v[52:53], off
	s_nop 0
	global_load_dwordx4 v[52:55], v[54:55], off offset:64
	s_and_saveexec_b64 s[54:55], s[52:53]
	s_cbranch_execz .LBB0_509
	v_add_u32_e32 v82, 0x4004, v90
	ds_read2_b32 v[82:83], v82 offset1:1
	ds_read_b32 v102, v90 offset:16396
	v_or_b32_e32 v101, s16, v89
	v_cmp_gt_i32_e32 vcc, v101, v74
	v_cmp_le_i32_e64 s[14:15], v101, v80
	s_and_b64 s[16:17], vcc, s[14:15]
	v_mov_b32_e32 v103, 0xf149f2ca
	s_and_saveexec_b64 s[14:15], s[16:17]
	s_cbranch_execz .LBB0_490
	ds_read_b32 v103, v90 offset:16384
	s_waitcnt lgkmcnt(0)
	v_max_f32_e32 v103, 0xf149f2ca, v103
.LBB0_490:
	s_or_b64 exec, exec, s[14:15]
	v_cmp_ge_i32_e32 vcc, v101, v74
	v_cmp_lt_i32_e64 s[14:15], v101, v80
	s_waitcnt lgkmcnt(1)
	v_max_f32_e32 v82, v103, v82
	s_and_b64 vcc, vcc, s[14:15]
	v_cndmask_b32_e32 v82, v103, v82, vcc
	v_or_b32_e32 v103, 2, v101
	v_cmp_gt_i32_e32 vcc, v103, v74
	v_cmp_le_i32_e64 s[14:15], v103, v80
	v_max_f32_e32 v83, v82, v83
	s_and_b64 vcc, vcc, s[14:15]
	v_cndmask_b32_e32 v82, v82, v83, vcc
	v_or_b32_e32 v83, 3, v101
	v_cmp_gt_i32_e32 vcc, v83, v74
	v_cmp_le_i32_e64 s[14:15], v83, v80
	s_waitcnt lgkmcnt(0)
	v_max_f32_e32 v83, v82, v102
	s_and_b64 vcc, vcc, s[14:15]
	v_cndmask_b32_e32 v103, v82, v83, vcc
	v_add_u32_e32 v82, 0x4014, v90
	ds_read2_b32 v[82:83], v82 offset1:1
	ds_read_b32 v102, v90 offset:16412
	v_or_b32_e32 v104, 4, v101
	v_cmp_gt_i32_e32 vcc, v104, v74
	v_cmp_le_i32_e64 s[14:15], v104, v80
	s_and_b64 s[16:17], vcc, s[14:15]
	s_and_saveexec_b64 s[14:15], s[16:17]
	s_cbranch_execz .LBB0_492
	ds_read_b32 v104, v90 offset:16400
	s_waitcnt lgkmcnt(0)
	v_max_f32_e32 v103, v103, v104
.LBB0_492:
	s_or_b64 exec, exec, s[14:15]
	v_or_b32_e32 v104, 5, v101
	v_cmp_gt_i32_e32 vcc, v104, v74
	v_cmp_le_i32_e64 s[14:15], v104, v80
	s_waitcnt lgkmcnt(1)
	v_max_f32_e32 v82, v103, v82
	s_and_b64 vcc, vcc, s[14:15]
	v_cndmask_b32_e32 v82, v103, v82, vcc
	v_or_b32_e32 v103, 6, v101
	v_cmp_gt_i32_e32 vcc, v103, v74
	v_cmp_le_i32_e64 s[14:15], v103, v80
	v_max_f32_e32 v83, v82, v83
	s_and_b64 vcc, vcc, s[14:15]
	v_cndmask_b32_e32 v82, v82, v83, vcc
	v_or_b32_e32 v83, 7, v101
	v_cmp_gt_i32_e32 vcc, v83, v74
	v_cmp_le_i32_e64 s[14:15], v83, v80
	s_waitcnt lgkmcnt(0)
	v_max_f32_e32 v83, v82, v102
	s_and_b64 vcc, vcc, s[14:15]
	v_cndmask_b32_e32 v103, v82, v83, vcc
	v_add_u32_e32 v82, 0x4024, v90
	ds_read2_b32 v[82:83], v82 offset1:1
	ds_read_b32 v102, v90 offset:16428
	v_or_b32_e32 v104, 8, v101
	v_cmp_gt_i32_e32 vcc, v104, v74
	v_cmp_le_i32_e64 s[14:15], v104, v80
	s_and_b64 s[16:17], vcc, s[14:15]
	s_and_saveexec_b64 s[14:15], s[16:17]
	s_cbranch_execz .LBB0_494
	ds_read_b32 v104, v90 offset:16416
	s_waitcnt lgkmcnt(0)
	v_max_f32_e32 v103, v103, v104
.LBB0_494:
	s_or_b64 exec, exec, s[14:15]
	v_or_b32_e32 v104, 9, v101
	v_cmp_gt_i32_e32 vcc, v104, v74
	v_cmp_le_i32_e64 s[14:15], v104, v80
	s_waitcnt lgkmcnt(1)
	v_max_f32_e32 v82, v103, v82
	s_and_b64 vcc, vcc, s[14:15]
	v_cndmask_b32_e32 v82, v103, v82, vcc
	v_or_b32_e32 v103, 10, v101
	v_cmp_gt_i32_e32 vcc, v103, v74
	v_cmp_le_i32_e64 s[14:15], v103, v80
	v_max_f32_e32 v83, v82, v83
	s_and_b64 vcc, vcc, s[14:15]
	v_cndmask_b32_e32 v82, v82, v83, vcc
	v_or_b32_e32 v83, 11, v101
	v_cmp_gt_i32_e32 vcc, v83, v74
	v_cmp_le_i32_e64 s[14:15], v83, v80
	s_waitcnt lgkmcnt(0)
	v_max_f32_e32 v83, v82, v102
	s_and_b64 vcc, vcc, s[14:15]
	v_cndmask_b32_e32 v103, v82, v83, vcc
	v_add_u32_e32 v82, 0x4034, v90
	ds_read2_b32 v[82:83], v82 offset1:1
	ds_read_b32 v102, v90 offset:16444
	v_or_b32_e32 v104, 12, v101
	v_cmp_gt_i32_e32 vcc, v104, v74
	v_cmp_le_i32_e64 s[14:15], v104, v80
	s_and_b64 s[16:17], vcc, s[14:15]
	s_and_saveexec_b64 s[14:15], s[16:17]
	s_cbranch_execz .LBB0_496
	ds_read_b32 v104, v90 offset:16432
	s_waitcnt lgkmcnt(0)
	v_max_f32_e32 v103, v103, v104
; template <int DH, int MODE>
; __device__ void attn_item(const Params& p, int layer, int b, int blk, int head, char* smem) {
;     ...
; #pragma unroll
;         for (int c = 0; c < 8; ++c) {
;           float4 v = s4[c];
;           float e[4] = {v.x, v.y, v.z, v.w};
; #pragma unroll
;           for (int k = 0; k < 4; ++k) {
;             int kj = kjb + c * 4 + k;
;             bool valid = (kj > row) && (kj <= row + 128);
;             tmax = valid ? fmaxf(tmax, e[k]) : tmax;
;           }
;         }
;         tmax = fmaxf(tmax, __shfl_xor(tmax, 1));
;         float m_new = fmaxf(m_run, tmax);
;         float alpha = __builtin_amdgcn_exp2f(m_run - m_new);
.LBB0_496:
	s_or_b64 exec, exec, s[14:15]
	v_or_b32_e32 v104, 13, v101
	v_cmp_gt_i32_e32 vcc, v104, v74
	v_cmp_le_i32_e64 s[14:15], v104, v80
	s_waitcnt lgkmcnt(1)
	v_max_f32_e32 v82, v103, v82
	s_and_b64 vcc, vcc, s[14:15]
	v_cndmask_b32_e32 v82, v103, v82, vcc
	v_or_b32_e32 v103, 14, v101
	v_cmp_gt_i32_e32 vcc, v103, v74
	v_cmp_le_i32_e64 s[14:15], v103, v80
	v_max_f32_e32 v83, v82, v83
	s_and_b64 vcc, vcc, s[14:15]
	v_cndmask_b32_e32 v82, v82, v83, vcc
	v_or_b32_e32 v83, 15, v101
	v_cmp_gt_i32_e32 vcc, v83, v74
	v_cmp_le_i32_e64 s[14:15], v83, v80
	s_waitcnt lgkmcnt(0)
	v_max_f32_e32 v83, v82, v102
	s_and_b64 vcc, vcc, s[14:15]
	v_cndmask_b32_e32 v103, v82, v83, vcc
	v_add_u32_e32 v82, 0x4044, v90
	ds_read2_b32 v[82:83], v82 offset1:1
	ds_read_b32 v102, v90 offset:16460
	v_or_b32_e32 v104, 16, v101
	v_cmp_gt_i32_e32 vcc, v104, v74
	v_cmp_le_i32_e64 s[14:15], v104, v80
	s_and_b64 s[16:17], vcc, s[14:15]
	s_and_saveexec_b64 s[14:15], s[16:17]
	s_cbranch_execz .LBB0_498
	ds_read_b32 v104, v90 offset:16448
	s_waitcnt lgkmcnt(0)
	v_max_f32_e32 v103, v103, v104
.LBB0_498:
	s_or_b64 exec, exec, s[14:15]
	v_or_b32_e32 v104, 17, v101
	v_cmp_gt_i32_e32 vcc, v104, v74
	v_cmp_le_i32_e64 s[14:15], v104, v80
	s_waitcnt lgkmcnt(1)
	v_max_f32_e32 v82, v103, v82
	s_and_b64 vcc, vcc, s[14:15]
	v_cndmask_b32_e32 v82, v103, v82, vcc
	v_or_b32_e32 v103, 18, v101
	v_cmp_gt_i32_e32 vcc, v103, v74
	v_cmp_le_i32_e64 s[14:15], v103, v80
	v_max_f32_e32 v83, v82, v83
	s_and_b64 vcc, vcc, s[14:15]
	v_cndmask_b32_e32 v82, v82, v83, vcc
	v_or_b32_e32 v83, 19, v101
	v_cmp_gt_i32_e32 vcc, v83, v74
	v_cmp_le_i32_e64 s[14:15], v83, v80
	s_waitcnt lgkmcnt(0)
	v_max_f32_e32 v83, v82, v102
	s_and_b64 vcc, vcc, s[14:15]
	v_cndmask_b32_e32 v103, v82, v83, vcc
	v_add_u32_e32 v82, 0x4054, v90
	ds_read2_b32 v[82:83], v82 offset1:1
	ds_read_b32 v102, v90 offset:16476
	v_or_b32_e32 v104, 20, v101
	v_cmp_gt_i32_e32 vcc, v104, v74
	v_cmp_le_i32_e64 s[14:15], v104, v80
	s_and_b64 s[16:17], vcc, s[14:15]
	s_and_saveexec_b64 s[14:15], s[16:17]
	s_cbranch_execz .LBB0_500
	ds_read_b32 v104, v90 offset:16464
	s_waitcnt lgkmcnt(0)
	v_max_f32_e32 v103, v103, v104
.LBB0_500:
	s_or_b64 exec, exec, s[14:15]
	v_or_b32_e32 v104, 21, v101
	v_cmp_gt_i32_e32 vcc, v104, v74
	v_cmp_le_i32_e64 s[14:15], v104, v80
	s_waitcnt lgkmcnt(1)
	v_max_f32_e32 v82, v103, v82
	s_and_b64 vcc, vcc, s[14:15]
	v_cndmask_b32_e32 v82, v103, v82, vcc
	v_or_b32_e32 v103, 22, v101
	v_cmp_gt_i32_e32 vcc, v103, v74
	v_cmp_le_i32_e64 s[14:15], v103, v80
	v_max_f32_e32 v83, v82, v83
	s_and_b64 vcc, vcc, s[14:15]
	v_cndmask_b32_e32 v82, v82, v83, vcc
	v_or_b32_e32 v83, 23, v101
	v_cmp_gt_i32_e32 vcc, v83, v74
	v_cmp_le_i32_e64 s[14:15], v83, v80
	s_waitcnt lgkmcnt(0)
	v_max_f32_e32 v83, v82, v102
	s_and_b64 vcc, vcc, s[14:15]
	v_cndmask_b32_e32 v103, v82, v83, vcc
	v_add_u32_e32 v82, 0x4064, v90
	ds_read2_b32 v[82:83], v82 offset1:1
	ds_read_b32 v102, v90 offset:16492
	v_or_b32_e32 v104, 24, v101
	v_cmp_gt_i32_e32 vcc, v104, v74
	v_cmp_le_i32_e64 s[14:15], v104, v80
	s_and_b64 s[16:17], vcc, s[14:15]
	s_and_saveexec_b64 s[14:15], s[16:17]
	s_cbranch_execz .LBB0_502
	ds_read_b32 v104, v90 offset:16480
	s_waitcnt lgkmcnt(0)
	v_max_f32_e32 v103, v103, v104
.LBB0_502:
	s_or_b64 exec, exec, s[14:15]
	v_or_b32_e32 v104, 25, v101
	v_cmp_gt_i32_e32 vcc, v104, v74
	v_cmp_le_i32_e64 s[14:15], v104, v80
	s_waitcnt lgkmcnt(1)
	v_max_f32_e32 v82, v103, v82
	s_and_b64 vcc, vcc, s[14:15]
	v_cndmask_b32_e32 v82, v103, v82, vcc
	v_or_b32_e32 v103, 26, v101
	v_cmp_gt_i32_e32 vcc, v103, v74
	v_cmp_le_i32_e64 s[14:15], v103, v80
	v_max_f32_e32 v83, v82, v83
	s_and_b64 vcc, vcc, s[14:15]
	v_cndmask_b32_e32 v82, v82, v83, vcc
	v_or_b32_e32 v83, 27, v101
	v_cmp_gt_i32_e32 vcc, v83, v74
	v_cmp_le_i32_e64 s[14:15], v83, v80
	s_waitcnt lgkmcnt(0)
	v_max_f32_e32 v83, v82, v102
	s_and_b64 vcc, vcc, s[14:15]
	v_cndmask_b32_e32 v103, v82, v83, vcc
	v_add_u32_e32 v82, 0x4074, v90
	ds_read2_b32 v[82:83], v82 offset1:1
	ds_read_b32 v102, v90 offset:16508
	v_or_b32_e32 v104, 28, v101
	v_cmp_gt_i32_e32 vcc, v104, v74
	v_cmp_le_i32_e64 s[14:15], v104, v80
	s_and_b64 s[16:17], vcc, s[14:15]
	s_and_saveexec_b64 s[14:15], s[16:17]
	s_cbranch_execz .LBB0_504
	ds_read_b32 v104, v90 offset:16496
	s_waitcnt lgkmcnt(0)
	v_max_f32_e32 v103, v103, v104
.LBB0_504:
	s_or_b64 exec, exec, s[14:15]
	v_or_b32_e32 v104, 29, v101
	v_cmp_gt_i32_e32 vcc, v104, v74
	v_cmp_le_i32_e64 s[14:15], v104, v80
	s_waitcnt lgkmcnt(1)
	v_max_f32_e32 v82, v103, v82
	s_and_b64 vcc, vcc, s[14:15]
	v_cndmask_b32_e32 v82, v103, v82, vcc
	v_or_b32_e32 v103, 30, v101
	v_cmp_gt_i32_e32 vcc, v103, v74
	v_cmp_le_i32_e64 s[14:15], v103, v80
	v_max_f32_e32 v83, v82, v83
	s_and_b64 vcc, vcc, s[14:15]
	v_cndmask_b32_e32 v82, v82, v83, vcc
	v_or_b32_e32 v83, 31, v101
	v_cmp_gt_i32_e32 vcc, v83, v74
	v_cmp_le_i32_e64 s[14:15], v83, v80
	s_waitcnt lgkmcnt(0)
	v_max_f32_e32 v83, v82, v102
	s_and_b64 vcc, vcc, s[14:15]
	v_cndmask_b32_e32 v82, v82, v83, vcc
	v_cmp_lt_i32_e32 vcc, v157, v158
	s_mov_b32 s90, 0
	v_mov_b32_e32 v103, 0
	v_cndmask_b32_e32 v83, v156, v157, vcc
	v_lshlrev_b32_e32 v83, 2, v83
	ds_bpermute_b32 v101, v83, v82
	v_mov_b32_e32 v102, v91
	s_waitcnt lgkmcnt(0)
	v_max3_f32 v82, v87, v82, v101
	v_mov_b32_e32 v101, v93
; __device__ __forceinline__ unsigned pack2(float a, float b) { return (unsigned)f2bf(a) | ((unsigned)f2bf(b) << 16); }
; template <int DH, int MODE>
; __device__ void attn_item(const Params& p, int layer, int b, int blk, int head, char* smem) {
;     ...
; #pragma unroll 2
;         for (int s8 = 0; s8 < 4; ++s8) {
;           float4 va = s4[2 * s8], vb = s4[2 * s8 + 1];
;           float e[8] = {va.x, va.y, va.z, va.w, vb.x, vb.y, vb.z, vb.w};
;           float pv[8];
; #pragma unroll
;           for (int k = 0; k < 8; ++k) {
;             int kj = kjb + s8 * 8 + k;
;             bool valid = (kj > row) && (kj <= row + 128);
;             float pe = valid ? __builtin_amdgcn_exp2f(e[k] - m_new) : 0.f;
;             pv[k] = pe;
;             psum += pe;
;           }
;           uint4 ov;
;           ov.x = pack2(pv[0], pv[1]); ov.y = pack2(pv[2], pv[3]);
;           ov.z = pack2(pv[4], pv[5]); ov.w = pack2(pv[6], pv[7]);
;           *reinterpret_cast<uint4*>(prow + s8 * 16) = ov;
;         }
;         psum += __shfl_xor(psum, 1);
;         l_run = l_run * alpha + psum;
;         m_run = m_new;
;         if (half == 0) alpha_s[row] = alpha;
.LBB0_505:
	ds_read_b128 v[104:107], v102
	ds_read_b128 v[108:111], v102 offset:16
	v_add_u32_e32 v112, s90, v92
	v_add_u32_e32 v113, 2, v112
	v_cmp_gt_i32_e64 s[14:15], v112, v74
	s_waitcnt lgkmcnt(1)
	v_sub_f32_e32 v104, v104, v82
	v_exp_f32_e32 v104, v104
	v_sub_f32_e32 v106, v106, v82
	v_sub_f32_e32 v105, v105, v82
	v_exp_f32_e32 v106, v106
	v_exp_f32_e32 v105, v105
	v_sub_f32_e32 v107, v107, v82
	v_cmp_le_i32_e64 s[20:21], v112, v80
	v_exp_f32_e32 v107, v107
	v_cmp_gt_i32_e32 vcc, v113, v65
	v_cmp_le_i32_e64 s[16:17], v113, v69
	s_and_b64 s[14:15], s[14:15], s[20:21]
	v_add_u32_e32 v114, 3, v112
	s_and_b64 vcc, vcc, s[16:17]
	v_cndmask_b32_e64 v104, 0, v104, s[14:15]
	v_cmp_lt_i32_e64 s[14:15], v112, v80
	v_cmp_ge_i32_e64 s[20:21], v112, v74
	v_cndmask_b32_e32 v106, 0, v106, vcc
	v_cmp_lt_i32_e32 vcc, v74, v114
	v_cmp_ge_i32_e64 s[16:17], v80, v114
	s_and_b64 s[14:15], s[14:15], s[20:21]
	v_add_f32_e32 v103, v103, v104
	s_and_b64 vcc, vcc, s[16:17]
	v_cndmask_b32_e64 v105, 0, v105, s[14:15]
	v_cndmask_b32_e32 v107, 0, v107, vcc
	v_add_f32_e32 v103, v103, v105
	v_add_f32_e32 v103, v103, v106
	v_cvt_pk_bf16_f32 v106, 0, v106
	s_waitcnt lgkmcnt(0)
	v_sub_f32_e32 v108, v108, v82
	v_sub_f32_e32 v110, v110, v82
	v_add_f32_e32 v103, v103, v107
	v_cvt_pk_bf16_f32 v104, 0, v104
	v_cvt_pk_bf16_f32 v107, 0, v107
	v_exp_f32_e32 v108, v108
	v_exp_f32_e32 v110, v110
	v_cvt_pk_bf16_f32 v105, 0, v105
	v_and_b32_e32 v107, 0xffff0000, v107
	v_sub_f32_e32 v109, v109, v82
	v_sub_f32_e32 v111, v111, v82
	v_and_b32_e32 v113, 0xffff0000, v105
	v_or_b32_sdwa v105, v107, v106 dst_sel:DWORD dst_unused:UNUSED_PAD src0_sel:DWORD src1_sel:WORD_1
	v_or_b32_e32 v106, 6, v112
	v_or_b32_e32 v107, 4, v112
	v_exp_f32_e32 v109, v109
	v_exp_f32_e32 v111, v111
	v_cmp_gt_i32_e32 vcc, v107, v74
	v_cmp_gt_i32_e64 s[14:15], v106, v65
	v_cmp_le_i32_e64 s[16:17], v107, v80
	v_cmp_le_i32_e64 s[20:21], v106, v69
	s_and_b64 s[14:15], s[14:15], s[20:21]
	s_and_b64 vcc, vcc, s[16:17]
	v_or_b32_e32 v106, 7, v112
	v_or_b32_e32 v107, 5, v112
	v_cndmask_b32_e32 v108, 0, v108, vcc
	v_cndmask_b32_e64 v110, 0, v110, s[14:15]
	v_cmp_gt_i32_e32 vcc, v107, v74
	v_cmp_gt_i32_e64 s[14:15], v106, v65
	v_cmp_le_i32_e64 s[16:17], v107, v80
	v_cmp_le_i32_e64 s[20:21], v106, v69
	s_and_b64 s[14:15], s[14:15], s[20:21]
	s_and_b64 vcc, vcc, s[16:17]
	v_cndmask_b32_e32 v109, 0, v109, vcc
	v_cndmask_b32_e64 v111, 0, v111, s[14:15]
	v_or_b32_sdwa v104, v113, v104 dst_sel:DWORD dst_unused:UNUSED_PAD src0_sel:DWORD src1_sel:WORD_1
	v_cvt_pk_bf16_f32 v113, 0, v108
	v_cvt_pk_bf16_f32 v107, 0, v111
	v_cvt_pk_bf16_f32 v114, 0, v109
	v_cvt_pk_bf16_f32 v106, 0, v110
	v_and_b32_e32 v107, 0xffff0000, v107
	v_and_b32_e32 v114, 0xffff0000, v114
	v_add_f32_e32 v103, v103, v108
	v_or_b32_sdwa v107, v107, v106 dst_sel:DWORD dst_unused:UNUSED_PAD src0_sel:DWORD src1_sel:WORD_1
	v_or_b32_sdwa v106, v114, v113 dst_sel:DWORD dst_unused:UNUSED_PAD src0_sel:DWORD src1_sel:WORD_1
	v_add_f32_e32 v103, v103, v109
	v_add_f32_e32 v103, v103, v110
	ds_write_b128 v101, v[104:107]
	v_add_f32_e32 v103, v103, v111
	ds_read_b128 v[104:107], v102 offset:32
	ds_read_b128 v[108:111], v102 offset:48
	v_add_u32_e32 v113, 8, v112
	v_add_u32_e32 v114, 10, v112
	v_cmp_gt_i32_e64 s[14:15], v113, v74
	s_waitcnt lgkmcnt(1)
	v_sub_f32_e32 v104, v104, v82
	v_exp_f32_e32 v104, v104
	v_sub_f32_e32 v106, v106, v82
	v_sub_f32_e32 v105, v105, v82
	v_exp_f32_e32 v106, v106
	v_exp_f32_e32 v105, v105
	v_sub_f32_e32 v107, v107, v82
	v_cmp_le_i32_e64 s[20:21], v113, v80
	v_exp_f32_e32 v107, v107
	v_cmp_gt_i32_e32 vcc, v114, v65
	v_cmp_le_i32_e64 s[16:17], v114, v69
	s_and_b64 s[14:15], s[14:15], s[20:21]
	v_add_u32_e32 v112, 11, v112
	s_and_b64 vcc, vcc, s[16:17]
	v_cndmask_b32_e64 v104, 0, v104, s[14:15]
	v_cmp_lt_i32_e64 s[14:15], v113, v80
	v_cmp_ge_i32_e64 s[20:21], v113, v74
	v_cndmask_b32_e32 v106, 0, v106, vcc
	v_cmp_lt_i32_e32 vcc, v74, v112
	v_cmp_ge_i32_e64 s[16:17], v80, v112
	s_and_b64 s[14:15], s[14:15], s[20:21]
	v_add_f32_e32 v103, v103, v104
	s_and_b64 vcc, vcc, s[16:17]
	v_cndmask_b32_e64 v105, 0, v105, s[14:15]
	v_cndmask_b32_e32 v107, 0, v107, vcc
	v_add_f32_e32 v103, v103, v105
	v_add_f32_e32 v103, v103, v106
	v_cvt_pk_bf16_f32 v106, 0, v106
	s_waitcnt lgkmcnt(0)
	v_sub_f32_e32 v108, v108, v82
	v_sub_f32_e32 v110, v110, v82
	v_add_f32_e32 v103, v103, v107
	v_cvt_pk_bf16_f32 v104, 0, v104
	v_cvt_pk_bf16_f32 v107, 0, v107
	v_exp_f32_e32 v108, v108
	v_exp_f32_e32 v110, v110
	v_cvt_pk_bf16_f32 v105, 0, v105
	v_and_b32_e32 v107, 0xffff0000, v107
	v_sub_f32_e32 v109, v109, v82
	v_sub_f32_e32 v111, v111, v82
	v_and_b32_e32 v112, 0xffff0000, v105
	v_or_b32_sdwa v105, v107, v106 dst_sel:DWORD dst_unused:UNUSED_PAD src0_sel:DWORD src1_sel:WORD_1
	v_or_b32_e32 v106, 6, v113
	v_or_b32_e32 v107, 4, v113
	v_exp_f32_e32 v109, v109
	v_exp_f32_e32 v111, v111
	v_cmp_gt_i32_e32 vcc, v107, v74
	v_cmp_gt_i32_e64 s[14:15], v106, v65
	v_cmp_le_i32_e64 s[16:17], v107, v80
	v_cmp_le_i32_e64 s[20:21], v106, v69
	s_and_b64 s[14:15], s[14:15], s[20:21]
	s_and_b64 vcc, vcc, s[16:17]
	v_or_b32_e32 v106, 7, v113
	v_or_b32_e32 v107, 5, v113
	v_cndmask_b32_e32 v108, 0, v108, vcc
	v_cndmask_b32_e64 v110, 0, v110, s[14:15]
	v_cmp_gt_i32_e32 vcc, v107, v74
	v_cmp_gt_i32_e64 s[14:15], v106, v65
	v_cmp_le_i32_e64 s[16:17], v107, v80
	v_cmp_le_i32_e64 s[20:21], v106, v69
	s_and_b64 s[14:15], s[14:15], s[20:21]
	s_and_b64 vcc, vcc, s[16:17]
	v_cndmask_b32_e32 v109, 0, v109, vcc
	v_cndmask_b32_e64 v111, 0, v111, s[14:15]
	v_or_b32_sdwa v104, v112, v104 dst_sel:DWORD dst_unused:UNUSED_PAD src0_sel:DWORD src1_sel:WORD_1
	v_cvt_pk_bf16_f32 v112, 0, v108
	v_cvt_pk_bf16_f32 v107, 0, v111
	v_cvt_pk_bf16_f32 v113, 0, v109
	v_add_f32_e32 v103, v103, v108
	v_cvt_pk_bf16_f32 v106, 0, v110
	v_and_b32_e32 v107, 0xffff0000, v107
	v_and_b32_e32 v113, 0xffff0000, v113
	v_add_f32_e32 v103, v103, v109
	v_or_b32_sdwa v107, v107, v106 dst_sel:DWORD dst_unused:UNUSED_PAD src0_sel:DWORD src1_sel:WORD_1
	v_or_b32_sdwa v106, v113, v112 dst_sel:DWORD dst_unused:UNUSED_PAD src0_sel:DWORD src1_sel:WORD_1
	v_add_f32_e32 v103, v103, v110
	s_add_i32 s90, s90, 16
	v_add_f32_e32 v103, v103, v111
	ds_write_b128 v101, v[104:107] offset:16
	v_add_u32_e32 v102, 64, v102
	v_add_u32_e32 v101, 32, v101
	s_cmp_eq_u32 s90, 32
	s_cbranch_scc0 .LBB0_505
	v_sub_f32_e32 v101, v87, v82
	ds_bpermute_b32 v87, v83, v103
	v_exp_f32_e32 v83, v101
	s_and_saveexec_b64 s[14:15], s[12:13]
	ds_write_b32 v97, v83 offset:8192
	s_or_b64 exec, exec, s[14:15]
	s_waitcnt lgkmcnt(0)
	v_add_f32_e32 v101, v103, v87
	v_fmac_f32_e32 v101, v88, v83
	v_mov_b32_e32 v87, v82
	v_mov_b32_e32 v88, v101

; template <int DH, int MODE>
; __device__ void attn_item(const Params& p, int layer, int b, int blk, int head, char* smem) {
;     ...
;   if (MODE == 0 && half == 0) linv_s[row] = 1.f / l_run;
;   __syncthreads();
;   {
;     constexpr int OST = DH + 4;
;     constexpr int CPR = DH / 8;
;     constexpr int NCH = 128 * CPR / 256;
;     float* Of = reinterpret_cast<float*>(smem);
;     uint4 gt[NCH];
; #pragma unroll
;     for (int i = 0; i < NCH; ++i) {
;       int q = tid + 256 * i, r = q / CPR, c = (q % CPR) * 8;
;       gt[i] = *reinterpret_cast<const uint4*>(P + (tq0 + r) * NP + gcol + c);
;     }
;     float lis[2][4];
; #pragma unroll
;     for (int m = 0; m < 2; ++m)
; #pragma unroll
;       for (int j = 0; j < 4; ++j) lis[m][j] = (MODE == 0) ? linv_s[wid * 32 + m * 16 + fq * 4 + j] : 1.f;
;     if (MODE == 0) __syncthreads();
; #pragma unroll
;     for (int m = 0; m < 2; ++m)
; #pragma unroll
;       for (int j = 0; j < 4; ++j) {
;         int r = wid * 32 + m * 16 + fq * 4 + j;
; #pragma unroll
;         for (int n = 0; n < NDT; ++n) Of[r * OST + n * 16 + fr] = o[m][n][j] * lis[m][j];
;       }
;     __syncthreads();
.LBB0_511:
	v_readfirstlane_b32 s16, v85
	s_and_saveexec_b64 s[14:15], s[12:13]
	s_cbranch_execz .LBB0_513
	v_rcp_f32_e32 v32, v88
	v_lshlrev_b32_e32 v33, 2, v74
	ds_write_b32 v33, v32 offset:8704
.LBB0_513:
	s_or_b64 exec, exec, s[14:15]
	v_lshl_add_u64 v[44:45], v[66:67], 0, s[36:37]
	v_mov_b64_e32 v[46:47], s[50:51]
	v_mad_u64_u32 v[32:33], s[14:15], v44, s63, v[46:47]
	v_mad_i32_i24 v33, v45, s63, v33
	v_lshl_add_u64 v[36:37], v[32:33], 0, v[70:71]
	v_add_u32_e32 v32, 0x100, v81
	v_ashrrev_i32_e32 v33, 31, v32
	v_lshrrev_b32_e32 v33, 29, v33
	v_add_u32_e32 v33, v32, v33
	v_ashrrev_i32_e32 v86, 3, v33
	v_and_b32_e32 v33, -8, v33
	v_sub_u32_e32 v85, v32, v33
	v_lshlrev_b32_e32 v32, 3, v85
	v_ashrrev_i32_e32 v33, 31, v32
	s_waitcnt vmcnt(2)
	v_add_u32_e32 v48, 0x200, v81
	v_lshlrev_b64 v[90:91], 1, v[32:33]
	v_ashrrev_i32_e32 v32, 31, v48
	v_lshrrev_b32_e32 v32, 29, v32
	v_add_u32_e32 v32, v48, v32
	v_ashrrev_i32_e32 v92, 3, v32
	v_and_b32_e32 v49, -8, v32
	v_add_u32_e32 v32, 0x300, v81
	v_ashrrev_i32_e32 v33, 31, v32
	v_lshrrev_b32_e32 v33, 29, v33
	v_ashrrev_i32_e32 v87, 31, v86
	v_add_u32_e32 v33, v32, v33
	v_lshl_add_u64 v[88:89], v[86:87], 0, s[36:37]
	v_ashrrev_i32_e32 v94, 3, v33
	v_and_b32_e32 v33, -8, v33
	v_mad_u64_u32 v[34:35], s[14:15], v88, s63, v[46:47]
	v_sub_u32_e32 v87, v32, v33
	v_ashrrev_i32_e32 v95, 31, v94
	v_mad_i32_i24 v35, v89, s63, v35
	v_lshlrev_b32_e32 v32, 3, v87
	v_lshl_add_u64 v[40:41], v[94:95], 0, s[36:37]
	v_lshl_add_u64 v[38:39], v[34:35], 0, v[90:91]
	v_mad_u64_u32 v[34:35], s[14:15], v40, s63, v[46:47]
	v_ashrrev_i32_e32 v33, 31, v32
	v_mad_i32_i24 v35, v41, s63, v35
	v_lshlrev_b64 v[42:43], 1, v[32:33]
	v_lshl_add_u64 v[32:33], v[34:35], 0, v[42:43]
	v_add_co_u32_e32 v32, vcc, s72, v32
	s_waitcnt lgkmcnt(0)
	s_nop 0
	v_addc_co_u32_e32 v33, vcc, 0, v33, vcc
	s_barrier
	global_load_dwordx4 v[32:35], v[32:33], off offset:512
	v_sub_u32_e32 v95, v48, v49
	v_ashrrev_i32_e32 v93, 31, v92
	v_lshlrev_b32_e32 v48, 3, v95
	v_lshl_add_u64 v[96:97], v[92:93], 0, s[36:37]
	v_mad_u64_u32 v[46:47], s[14:15], v96, s63, v[46:47]
	v_ashrrev_i32_e32 v49, 31, v48
	v_mad_i32_i24 v47, v97, s63, v47
	v_lshlrev_b64 v[98:99], 1, v[48:49]
	v_lshl_add_u64 v[100:101], v[46:47], 0, v[98:99]
	v_lshl_or_b32 v46, v75, 7, v128
	ds_read_b128 v[60:63], v46 offset:8704
	ds_read_b128 v[80:83], v46 offset:8768
	s_ashr_i32 s13, s16, 31
	s_add_u32 s12, s28, s16
	s_addc_u32 s13, s29, s13
	s_lshl_b32 s14, s83, 1
	s_add_u32 s12, s12, s14
	v_lshl_or_b32 v46, v84, 2, v64
	s_waitcnt lgkmcnt(0)
	v_mul_f32_e32 v69, v0, v80
	s_addc_u32 s13, s13, 0
	v_mul_lo_u32 v0, v66, s74
	v_mul_lo_u32 v46, v46, s74
	v_mul_f32_e32 v75, v1, v81
	v_lshl_add_u32 v66, v68, 2, v0
	v_mov_b64_e32 v[0:1], s[12:13]
	v_lshl_add_u32 v47, v73, 2, v46
	v_mul_f32_e32 v48, v16, v60
	v_mul_f32_e32 v49, v28, v60
	v_mul_f32_e32 v50, v24, v60
	v_mul_f32_e32 v51, v20, v60
	s_waitcnt vmcnt(1)
	v_mul_f32_e32 v52, v17, v61
	v_mul_f32_e32 v53, v29, v61
	v_mul_f32_e32 v54, v25, v61
	v_mul_f32_e32 v55, v21, v61
	v_mul_f32_e32 v56, v18, v62
	v_mul_f32_e32 v57, v30, v62
	v_mul_f32_e32 v58, v26, v62
	v_mul_f32_e32 v59, v22, v62
	v_mul_f32_e32 v60, v19, v63
	v_mul_f32_e32 v61, v31, v63
	v_mul_f32_e32 v62, v27, v63
	v_mul_f32_e32 v64, v23, v63
	v_mul_f32_e32 v63, v12, v80
	v_mul_f32_e32 v65, v8, v80
	v_mul_f32_e32 v67, v4, v80
	v_mul_f32_e32 v72, v13, v81
	v_mul_f32_e32 v73, v9, v81
	v_mul_f32_e32 v74, v5, v81
	v_mul_f32_e32 v76, v14, v82
	v_mul_f32_e32 v77, v10, v82
	v_mul_f32_e32 v78, v6, v82
	v_mul_f32_e32 v80, v2, v82
	v_mul_f32_e32 v79, v15, v83
	v_mul_f32_e32 v81, v11, v83
	v_mul_f32_e32 v82, v7, v83
	v_mul_f32_e32 v83, v3, v83
	v_mad_u64_u32 v[2:3], s[12:13], v44, s70, v[0:1]
	v_mad_i32_i24 v3, v45, s70, v3
	v_lshl_add_u64 v[12:13], v[2:3], 0, v[70:71]
	v_mul_lo_u32 v2, v86, s74
	v_lshl_add_u32 v46, v85, 5, v2
	v_mad_u64_u32 v[2:3], s[12:13], v88, s70, v[0:1]
	v_mad_i32_i24 v3, v89, s70, v3
	v_mad_u64_u32 v[4:5], s[12:13], v40, s70, v[0:1]
	v_lshl_add_u64 v[10:11], v[2:3], 0, v[90:91]
	v_mul_lo_u32 v2, v92, s74
	v_mad_i32_i24 v5, v41, s70, v5
	v_lshl_add_u32 v45, v95, 5, v2
	v_mad_u64_u32 v[2:3], s[12:13], v96, s70, v[0:1]
	v_lshl_add_u64 v[14:15], v[4:5], 0, v[42:43]
	v_mad_i32_i24 v3, v97, s70, v3
	v_add_co_u32_e32 v0, vcc, s72, v100
	v_lshl_add_u64 v[8:9], v[2:3], 0, v[98:99]
	v_mul_lo_u32 v2, v94, s74
	s_waitcnt vmcnt(0)
	v_lshlrev_b32_e32 v16, 16, v33
	v_lshlrev_b32_e32 v18, 16, v32
	v_mul_f32_e32 v6, 0xbfb8aa3b, v18
	v_mul_f32_e32 v7, 0xbfb8aa3b, v16
	v_exp_f32_e32 v6, v6
	v_exp_f32_e32 v7, v7
	v_addc_co_u32_e32 v1, vcc, 0, v101, vcc
	v_lshl_add_u32 v44, v87, 5, v2
	v_pk_add_f32 v[4:5], v[6:7], 1.0 op_sel_hi:[1,0]
	global_load_dwordx4 v[0:3], v[0:1], off offset:512
	v_and_b32_e32 v19, 0xffff0000, v33
	v_and_b32_e32 v20, 0xffff0000, v32
	v_mul_f32_e32 v6, 0xbfb8aa3b, v20
	v_rcp_f32_e32 v17, v5
	s_nop 0
	v_mul_f32_e32 v17, v16, v17
	v_mul_f32_e32 v7, 0xbfb8aa3b, v19
	v_exp_f32_e32 v6, v6
	v_exp_f32_e32 v7, v7
	s_nop 0
	v_pk_add_f32 v[6:7], v[6:7], 1.0 op_sel_hi:[1,0]
	v_rcp_f32_e32 v16, v4
	s_nop 0
	v_mul_f32_e32 v16, v18, v16
	v_lshlrev_b32_e32 v23, 16, v34
	v_rcp_f32_e32 v4, v7
	s_nop 0
	v_mul_f32_e32 v19, v19, v4
	v_lshlrev_b32_e32 v22, 16, v35
	v_mul_f32_e32 v4, 0xbfb8aa3b, v23
	v_mul_f32_e32 v5, 0xbfb8aa3b, v22
	v_exp_f32_e32 v4, v4
	v_exp_f32_e32 v5, v5
	v_rcp_f32_e32 v18, v6
	s_nop 0
	v_mul_f32_e32 v18, v20, v18
	v_and_b32_e32 v24, 0xffff0000, v35
	v_pk_add_f32 v[4:5], v[4:5], 1.0 op_sel_hi:[1,0]
	v_and_b32_e32 v25, 0xffff0000, v34
	v_mul_f32_e32 v6, 0xbfb8aa3b, v25
	v_exp_f32_e32 v6, v6
	v_rcp_f32_e32 v21, v5
	s_nop 0
	v_mul_f32_e32 v21, v22, v21
	v_mul_f32_e32 v7, 0xbfb8aa3b, v24
	v_exp_f32_e32 v7, v7
	s_nop 0
	v_pk_add_f32 v[6:7], v[6:7], 1.0 op_sel_hi:[1,0]
	v_rcp_f32_e32 v20, v4
	s_nop 0
	v_mul_f32_e32 v20, v23, v20
	v_rcp_f32_e32 v23, v7
	s_nop 0
	v_mul_f32_e32 v23, v24, v23
	s_waitcnt vmcnt(0)
; __device__ __forceinline__ unsigned pack2(float a, float b) { return (unsigned)f2bf(a) | ((unsigned)f2bf(b) << 16); }
; __device__ __forceinline__ float bflo(unsigned w) { return __uint_as_float(w << 16); }
; __device__ __forceinline__ float bfhi(unsigned w) { return __uint_as_float(w & 0xffff0000u); }
; __device__ __forceinline__ float silu_f(float g) { return g / (1.f + __expf(-g)); }
; template <int DH, int MODE>
; __device__ void attn_item(const Params& p, int layer, int b, int blk, int head, char* smem) {
;     ...
; #pragma unroll
;     for (int m = 0; m < 2; ++m)
; #pragma unroll
;       for (int j = 0; j < 4; ++j) {
;         int r = wid * 32 + m * 16 + fq * 4 + j;
; #pragma unroll
;         for (int n = 0; n < NDT; ++n) Of[r * OST + n * 16 + fr] = o[m][n][j] * lis[m][j];
;       }
;     __syncthreads();
; #pragma unroll
;     for (int i = 0; i < NCH; ++i) {
;       int q = tid + 256 * i, r = q / CPR, c = (q % CPR) * 8;
;       float4 m0 = *reinterpret_cast<const float4*>(Of + r * OST + c);
;       float4 m1 = *reinterpret_cast<const float4*>(Of + r * OST + c + 4);
;       float mm[8] = {m0.x, m0.y, m0.z, m0.w, m1.x, m1.y, m1.z, m1.w};
;       unsigned gw[4] = {gt[i].x, gt[i].y, gt[i].z, gt[i].w};
;       unsigned ow[4];
; #pragma unroll
;       for (int e = 0; e < 4; ++e)
;         ow[e] = pack2(mm[2 * e] * silu_f(bflo(gw[e])), mm[2 * e + 1] * silu_f(bfhi(gw[e])));
	v_lshlrev_b32_e32 v24, 16, v1
	v_lshlrev_b32_e32 v26, 16, v0
	v_mul_f32_e32 v4, 0xbfb8aa3b, v26
	v_mul_f32_e32 v5, 0xbfb8aa3b, v24
	v_exp_f32_e32 v4, v4
	v_exp_f32_e32 v5, v5
	v_and_b32_e32 v27, 0xffff0000, v1
	v_rcp_f32_e32 v22, v6
	s_nop 0
	v_mul_f32_e32 v22, v25, v22
	v_pk_add_f32 v[4:5], v[4:5], 1.0 op_sel_hi:[1,0]
	v_and_b32_e32 v28, 0xffff0000, v0
	v_mul_f32_e32 v0, 0xbfb8aa3b, v28
	v_exp_f32_e32 v6, v0
	v_lshlrev_b32_e32 v32, 16, v3
	v_mul_f32_e32 v7, 0xbfb8aa3b, v27
	v_rcp_f32_e32 v1, v5
	s_nop 0
	v_mul_f32_e32 v1, v24, v1
	v_exp_f32_e32 v7, v7
	s_nop 0
	v_pk_add_f32 v[24:25], v[6:7], 1.0 op_sel_hi:[1,0]
	v_rcp_f32_e32 v0, v4
	s_nop 0
	v_mul_f32_e32 v0, v26, v0
	v_lshlrev_b32_e32 v33, 16, v2
	v_rcp_f32_e32 v25, v25
	s_nop 0
	v_mul_f32_e32 v25, v27, v25
	v_add_co_u32_e64 v4, s[12:13], s72, v38
	s_nop 0
	s_nop 0
	v_addc_co_u32_e64 v5, s[12:13], 0, v39, s[12:13]
	global_load_dwordx4 v[4:7], v[4:5], off offset:512
	v_mul_f32_e32 v26, 0xbfb8aa3b, v33
	v_mul_f32_e32 v27, 0xbfb8aa3b, v32
	v_exp_f32_e32 v26, v26
	v_exp_f32_e32 v27, v27
	v_and_b32_e32 v30, 0xffff0000, v3
	v_rcp_f32_e32 v24, v24
	s_nop 0
	v_mul_f32_e32 v24, v28, v24
	v_pk_add_f32 v[26:27], v[26:27], 1.0 op_sel_hi:[1,0]
	v_and_b32_e32 v38, 0xffff0000, v2
	v_mul_f32_e32 v2, 0xbfb8aa3b, v38
	v_exp_f32_e32 v28, v2
	v_mul_f32_e32 v29, 0xbfb8aa3b, v30
	v_exp_f32_e32 v29, v29
	v_rcp_f32_e32 v3, v27
	s_nop 0
	v_mul_f32_e32 v3, v32, v3
	v_pk_add_f32 v[28:29], v[28:29], 1.0 op_sel_hi:[1,0]
	v_rcp_f32_e32 v2, v26
	s_nop 0
	v_mul_f32_e32 v2, v33, v2
	v_rcp_f32_e32 v27, v29
	s_nop 0
	v_mul_f32_e32 v27, v30, v27
	v_add_co_u32_e64 v30, s[12:13], s72, v36
	s_nop 0
	s_nop 0
	v_addc_co_u32_e64 v31, s[12:13], 0, v37, s[12:13]
	global_load_dwordx4 v[32:35], v[30:31], off offset:512
	v_rcp_f32_e32 v26, v28
	s_nop 0
	v_mul_f32_e32 v26, v38, v26
	s_barrier
	s_waitcnt vmcnt(1)
	v_lshlrev_b32_e32 v36, 16, v5
	v_lshlrev_b32_e32 v37, 16, v4
	v_mul_f32_e32 v30, 0xbfb8aa3b, v37
	v_mul_f32_e32 v31, 0xbfb8aa3b, v36
	v_exp_f32_e32 v30, v30
	v_exp_f32_e32 v31, v31
	v_and_b32_e32 v38, 0xffff0000, v5
	v_and_b32_e32 v39, 0xffff0000, v4
	v_mul_f32_e32 v4, 0xbfb8aa3b, v39
	v_pk_add_f32 v[28:29], v[30:31], 1.0 op_sel_hi:[1,0]
	v_exp_f32_e32 v30, v4
	ds_write2_b32 v47, v48, v49 offset1:16
	ds_write2_b32 v47, v50, v51 offset0:32 offset1:48
	ds_write2_b32 v47, v52, v53 offset0:68 offset1:84
	ds_write2_b32 v47, v54, v55 offset0:100 offset1:116
	ds_write2_b32 v47, v56, v57 offset0:136 offset1:152
	ds_write2_b32 v47, v58, v59 offset0:168 offset1:184
	ds_write2_b32 v47, v60, v61 offset0:204 offset1:220
	ds_write2_b32 v47, v62, v64 offset0:236 offset1:252
	v_mul_f32_e32 v31, 0xbfb8aa3b, v38
	v_exp_f32_e32 v31, v31
	v_rcp_f32_e32 v5, v29
	s_nop 0
	v_mul_f32_e32 v5, v36, v5
	v_pk_add_f32 v[30:31], v[30:31], 1.0 op_sel_hi:[1,0]
	v_rcp_f32_e32 v4, v28
	s_nop 0
	v_mul_f32_e32 v4, v37, v4
	v_rcp_f32_e32 v29, v31
	s_nop 0
	v_mul_f32_e32 v29, v38, v29
	v_lshlrev_b32_e32 v38, 16, v7
	v_lshlrev_b32_e32 v40, 16, v6
	v_mul_f32_e32 v36, 0xbfb8aa3b, v40
	v_mul_f32_e32 v37, 0xbfb8aa3b, v38
	v_exp_f32_e32 v36, v36
	v_exp_f32_e32 v37, v37
	v_rcp_f32_e32 v28, v30
	s_nop 0
	v_mul_f32_e32 v28, v39, v28
	v_and_b32_e32 v39, 0xffff0000, v7
	v_pk_add_f32 v[30:31], v[36:37], 1.0 op_sel_hi:[1,0]
	v_and_b32_e32 v41, 0xffff0000, v6
	v_mul_f32_e32 v6, 0xbfb8aa3b, v41
	v_exp_f32_e32 v36, v6
	v_mul_f32_e32 v37, 0xbfb8aa3b, v39
	v_exp_f32_e32 v37, v37
	v_rcp_f32_e32 v7, v31
	s_nop 0
	v_mul_f32_e32 v7, v38, v7
	v_pk_add_f32 v[36:37], v[36:37], 1.0 op_sel_hi:[1,0]
	v_rcp_f32_e32 v6, v30
	s_nop 0
	v_mul_f32_e32 v6, v40, v6
	v_rcp_f32_e32 v31, v37
	s_nop 0
	v_mul_f32_e32 v31, v39, v31
	s_waitcnt vmcnt(0)
	v_lshlrev_b32_e32 v42, 16, v33
	v_lshlrev_b32_e32 v43, 16, v32
	v_mul_f32_e32 v38, 0xbfb8aa3b, v43
	v_mul_f32_e32 v39, 0xbfb8aa3b, v42
	v_exp_f32_e32 v38, v38
	v_exp_f32_e32 v39, v39
	v_rcp_f32_e32 v30, v36
	s_nop 0
	v_mul_f32_e32 v30, v41, v30
	v_and_b32_e32 v68, 0xffff0000, v33
	v_pk_add_f32 v[36:37], v[38:39], 1.0 op_sel_hi:[1,0]
	v_and_b32_e32 v39, 0xffff0000, v32
	v_mul_f32_e32 v32, 0xbfb8aa3b, v39
	v_exp_f32_e32 v32, v32
	v_rcp_f32_e32 v41, v37
	s_nop 0
	v_mul_f32_e32 v41, v42, v41
	v_mul_f32_e32 v33, 0xbfb8aa3b, v68
	v_exp_f32_e32 v33, v33
	s_nop 0
	v_pk_add_f32 v[32:33], v[32:33], 1.0 op_sel_hi:[1,0]
	v_rcp_f32_e32 v40, v36
	s_nop 0
	v_mul_f32_e32 v40, v43, v40
	v_lshlrev_b32_e32 v70, 16, v34
	v_rcp_f32_e32 v43, v33
	s_nop 0
	v_mul_f32_e32 v43, v68, v43
	v_lshlrev_b32_e32 v38, 16, v35
	v_mul_f32_e32 v36, 0xbfb8aa3b, v70
	v_mul_f32_e32 v37, 0xbfb8aa3b, v38
	v_exp_f32_e32 v36, v36
	v_exp_f32_e32 v37, v37
	v_rcp_f32_e32 v42, v32
	s_nop 0
	v_mul_f32_e32 v42, v39, v42
	v_and_b32_e32 v39, 0xffff0000, v35
	v_pk_add_f32 v[32:33], v[36:37], 1.0 op_sel_hi:[1,0]
	v_and_b32_e32 v68, 0xffff0000, v34
	v_mul_f32_e32 v34, 0xbfb8aa3b, v68
	v_exp_f32_e32 v34, v34
	v_rcp_f32_e32 v71, v33
	s_nop 0
	v_mul_f32_e32 v71, v38, v71
	v_mul_f32_e32 v35, 0xbfb8aa3b, v39
	v_exp_f32_e32 v35, v35
	s_nop 0
	v_pk_add_f32 v[36:37], v[34:35], 1.0 op_sel_hi:[1,0]
	v_rcp_f32_e32 v33, v32
	s_nop 0
	v_mul_f32_e32 v70, v70, v33
	v_rcp_f32_e32 v85, v37
	s_nop 0
	v_mul_f32_e32 v85, v39, v85
	v_add_u32_e32 v32, 0x1000, v47
	ds_write2_b32 v32, v63, v65 offset0:64 offset1:80
	ds_write2_b32 v32, v67, v69 offset0:96 offset1:112
	ds_write2_b32 v32, v72, v73 offset0:132 offset1:148
	ds_write2_b32 v32, v74, v75 offset0:164 offset1:180
	ds_write2_b32 v32, v76, v77 offset0:200 offset1:216
	ds_write2_b32 v32, v78, v80 offset0:232 offset1:248
	v_add_u32_e32 v32, 0x1400, v47
	ds_write2_b32 v32, v79, v81 offset0:12 offset1:28
	ds_write2_b32 v32, v82, v83 offset0:44 offset1:60
	s_waitcnt lgkmcnt(0)
	s_barrier
; __device__ __forceinline__ unsigned pack2(float a, float b) { return (unsigned)f2bf(a) | ((unsigned)f2bf(b) << 16); }
; __device__ __forceinline__ float bflo(unsigned w) { return __uint_as_float(w << 16); }
; __device__ __forceinline__ float bfhi(unsigned w) { return __uint_as_float(w & 0xffff0000u); }
; __device__ __forceinline__ float silu_f(float g) { return g / (1.f + __expf(-g)); }
; template <int DH, int MODE>
; __device__ void attn_item(const Params& p, int layer, int b, int blk, int head, char* smem) {
;     ...
; #pragma unroll
;     for (int i = 0; i < NCH; ++i) {
;       int q = tid + 256 * i, r = q / CPR, c = (q % CPR) * 8;
;       float4 m0 = *reinterpret_cast<const float4*>(Of + r * OST + c);
;       float4 m1 = *reinterpret_cast<const float4*>(Of + r * OST + c + 4);
;       float mm[8] = {m0.x, m0.y, m0.z, m0.w, m1.x, m1.y, m1.z, m1.w};
;       unsigned gw[4] = {gt[i].x, gt[i].y, gt[i].z, gt[i].w};
;       unsigned ow[4];
; #pragma unroll
;       for (int e = 0; e < 4; ++e)
;         ow[e] = pack2(mm[2 * e] * silu_f(bflo(gw[e])), mm[2 * e + 1] * silu_f(bfhi(gw[e])));
;       *reinterpret_cast<uint4*>(Y + (tq0 + r) * YW + ycol + c) = make_uint4(ow[0], ow[1], ow[2], ow[3]);
;     }
	ds_read_b128 v[32:35], v66
	v_rcp_f32_e32 v84, v36
	s_nop 0
	v_mul_f32_e32 v84, v68, v84
	ds_read_b128 v[36:39], v66 offset:16
	v_add_co_u32_e32 v12, vcc, s77, v12
	s_waitcnt lgkmcnt(1)
	v_mov_b32_e32 v48, v32
	v_mov_b32_e32 v49, v34
	v_pk_mul_f32 v[40:41], v[40:41], v[48:49]
	v_mov_b32_e32 v34, v33
	v_pk_mul_f32 v[32:33], v[42:43], v[34:35]
	v_cvt_pk_bf16_f32 v35, 0, v40
	v_cvt_pk_bf16_f32 v34, 0, v41
	v_cvt_pk_bf16_f32 v33, 0, v33
	v_cvt_pk_bf16_f32 v32, 0, v32
	v_and_b32_e32 v33, 0xffff0000, v33
	v_and_b32_e32 v32, 0xffff0000, v32
	v_or_b32_sdwa v33, v33, v34 dst_sel:DWORD dst_unused:UNUSED_PAD src0_sel:DWORD src1_sel:WORD_1
	v_or_b32_sdwa v32, v32, v35 dst_sel:DWORD dst_unused:UNUSED_PAD src0_sel:DWORD src1_sel:WORD_1
	s_waitcnt lgkmcnt(0)
	v_mov_b32_e32 v34, v36
	v_mov_b32_e32 v35, v38
	v_pk_mul_f32 v[34:35], v[70:71], v[34:35]
	v_mov_b32_e32 v38, v37
	v_pk_mul_f32 v[36:37], v[84:85], v[38:39]
	v_cvt_pk_bf16_f32 v34, 0, v34
	v_cvt_pk_bf16_f32 v35, 0, v35
	v_cvt_pk_bf16_f32 v37, 0, v37
	v_cvt_pk_bf16_f32 v36, 0, v36
	v_and_b32_e32 v37, 0xffff0000, v37
	v_and_b32_e32 v36, 0xffff0000, v36
	v_or_b32_sdwa v35, v37, v35 dst_sel:DWORD dst_unused:UNUSED_PAD src0_sel:DWORD src1_sel:WORD_1
	v_or_b32_sdwa v34, v36, v34 dst_sel:DWORD dst_unused:UNUSED_PAD src0_sel:DWORD src1_sel:WORD_1
	ds_read_b128 v[36:39], v46
	v_addc_co_u32_e32 v13, vcc, 0, v13, vcc
	global_store_dwordx4 v[12:13], v[32:35], off offset:1024
	s_nop 0
	ds_read_b128 v[32:35], v46 offset:16
	s_waitcnt lgkmcnt(1)
	v_mov_b32_e32 v12, v36
	v_mov_b32_e32 v13, v38
	v_pk_mul_f32 v[4:5], v[4:5], v[12:13]
	v_mov_b32_e32 v38, v37
	v_pk_mul_f32 v[12:13], v[28:29], v[38:39]
	v_cvt_pk_bf16_f32 v4, 0, v4
	v_cvt_pk_bf16_f32 v5, 0, v5
	v_cvt_pk_bf16_f32 v13, 0, v13
	v_cvt_pk_bf16_f32 v12, 0, v12
	v_and_b32_e32 v13, 0xffff0000, v13
	v_and_b32_e32 v12, 0xffff0000, v12
	v_or_b32_sdwa v5, v13, v5 dst_sel:DWORD dst_unused:UNUSED_PAD src0_sel:DWORD src1_sel:WORD_1
	v_or_b32_sdwa v4, v12, v4 dst_sel:DWORD dst_unused:UNUSED_PAD src0_sel:DWORD src1_sel:WORD_1
	s_waitcnt lgkmcnt(0)
	v_mov_b32_e32 v12, v32
	v_mov_b32_e32 v13, v34
	v_pk_mul_f32 v[6:7], v[6:7], v[12:13]
	v_mov_b32_e32 v34, v33
	v_pk_mul_f32 v[12:13], v[30:31], v[34:35]
	v_cvt_pk_bf16_f32 v6, 0, v6
	v_cvt_pk_bf16_f32 v7, 0, v7
	v_cvt_pk_bf16_f32 v13, 0, v13
	v_cvt_pk_bf16_f32 v12, 0, v12
	ds_read_b128 v[28:31], v45
	v_and_b32_e32 v13, 0xffff0000, v13
	v_and_b32_e32 v12, 0xffff0000, v12
	v_add_co_u32_e32 v10, vcc, s77, v10
	v_or_b32_sdwa v7, v13, v7 dst_sel:DWORD dst_unused:UNUSED_PAD src0_sel:DWORD src1_sel:WORD_1
	v_or_b32_sdwa v6, v12, v6 dst_sel:DWORD dst_unused:UNUSED_PAD src0_sel:DWORD src1_sel:WORD_1
	v_addc_co_u32_e32 v11, vcc, 0, v11, vcc
	global_store_dwordx4 v[10:11], v[4:7], off offset:1024
	s_waitcnt lgkmcnt(0)
	v_mov_b32_e32 v10, v28
	v_mov_b32_e32 v11, v30
	ds_read_b128 v[4:7], v45 offset:16
	v_pk_mul_f32 v[0:1], v[0:1], v[10:11]
	v_mov_b32_e32 v30, v29
	v_pk_mul_f32 v[10:11], v[24:25], v[30:31]
	v_cvt_pk_bf16_f32 v0, 0, v0
	v_cvt_pk_bf16_f32 v1, 0, v1
	v_cvt_pk_bf16_f32 v11, 0, v11
	v_cvt_pk_bf16_f32 v10, 0, v10
	v_and_b32_e32 v11, 0xffff0000, v11
	v_and_b32_e32 v10, 0xffff0000, v10
	v_or_b32_sdwa v1, v11, v1 dst_sel:DWORD dst_unused:UNUSED_PAD src0_sel:DWORD src1_sel:WORD_1
	v_or_b32_sdwa v0, v10, v0 dst_sel:DWORD dst_unused:UNUSED_PAD src0_sel:DWORD src1_sel:WORD_1
	s_waitcnt lgkmcnt(0)
	v_mov_b32_e32 v10, v4
	v_mov_b32_e32 v11, v6
	v_pk_mul_f32 v[2:3], v[2:3], v[10:11]
	v_mov_b32_e32 v6, v5
	v_pk_mul_f32 v[4:5], v[26:27], v[6:7]
	v_cvt_pk_bf16_f32 v2, 0, v2
	v_cvt_pk_bf16_f32 v3, 0, v3
	v_cvt_pk_bf16_f32 v5, 0, v5
	v_cvt_pk_bf16_f32 v4, 0, v4
	v_and_b32_e32 v5, 0xffff0000, v5
	v_and_b32_e32 v4, 0xffff0000, v4
	v_or_b32_sdwa v3, v5, v3 dst_sel:DWORD dst_unused:UNUSED_PAD src0_sel:DWORD src1_sel:WORD_1
	v_or_b32_sdwa v2, v4, v2 dst_sel:DWORD dst_unused:UNUSED_PAD src0_sel:DWORD src1_sel:WORD_1
	ds_read_b128 v[4:7], v44
	v_add_co_u32_e32 v8, vcc, s77, v8
	s_nop 1
	v_addc_co_u32_e32 v9, vcc, 0, v9, vcc
	global_store_dwordx4 v[8:9], v[0:3], off offset:1024
	s_waitcnt lgkmcnt(0)
	v_mov_b32_e32 v8, v4
	v_mov_b32_e32 v9, v6
	ds_read_b128 v[0:3], v44 offset:16
	v_pk_mul_f32 v[8:9], v[16:17], v[8:9]
	v_mov_b32_e32 v6, v5
	v_pk_mul_f32 v[4:5], v[18:19], v[6:7]
	v_cvt_pk_bf16_f32 v7, 0, v8
	v_cvt_pk_bf16_f32 v6, 0, v9
	v_cvt_pk_bf16_f32 v5, 0, v5
	v_cvt_pk_bf16_f32 v4, 0, v4
	v_and_b32_e32 v5, 0xffff0000, v5
	v_and_b32_e32 v4, 0xffff0000, v4
	v_or_b32_sdwa v5, v5, v6 dst_sel:DWORD dst_unused:UNUSED_PAD src0_sel:DWORD src1_sel:WORD_1
	v_or_b32_sdwa v4, v4, v7 dst_sel:DWORD dst_unused:UNUSED_PAD src0_sel:DWORD src1_sel:WORD_1
	s_waitcnt lgkmcnt(0)
	v_mov_b32_e32 v6, v0
	v_mov_b32_e32 v7, v2
	v_pk_mul_f32 v[6:7], v[20:21], v[6:7]
	v_mov_b32_e32 v2, v1
	v_pk_mul_f32 v[0:1], v[22:23], v[2:3]
	v_cvt_pk_bf16_f32 v2, 0, v7
	v_cvt_pk_bf16_f32 v3, 0, v6
	v_cvt_pk_bf16_f32 v0, 0, v0
	v_cvt_pk_bf16_f32 v1, 0, v1
	v_and_b32_e32 v0, 0xffff0000, v0
	v_and_b32_e32 v1, 0xffff0000, v1
	v_or_b32_sdwa v6, v0, v3 dst_sel:DWORD dst_unused:UNUSED_PAD src0_sel:DWORD src1_sel:WORD_1
	v_add_co_u32_e32 v0, vcc, 0x184a1000, v14
	v_or_b32_sdwa v7, v1, v2 dst_sel:DWORD dst_unused:UNUSED_PAD src0_sel:DWORD src1_sel:WORD_1
	s_nop 0
	v_addc_co_u32_e32 v1, vcc, 0, v15, vcc
	global_store_dwordx4 v[0:1], v[4:7], off offset:1024
	s_barrier

; __device__ __forceinline__ unsigned pack2(float a, float b) { return (unsigned)f2bf(a) | ((unsigned)f2bf(b) << 16); }
; template <int DH, int MODE>
; __device__ void attn_item(const Params& p, int layer, int b, int blk, int head, char* smem) {
;     ...
; #pragma unroll 2
;         for (int c = 7; c >= 0; --c) {
;           float4 v = s4[c];
;           float e[4] = {v.x, v.y, v.z, v.w};
; #pragma unroll
;           for (int k = 3; k >= 0; --k) {
;             float z = e[k];
;             bool valid = (kpb + c * 4 + k) < qpos;
;             float sp = fmaxf(z, 0.f) + __builtin_amdgcn_logf(1.f + __builtin_amdgcn_exp2f(-fabsf(z)));
;             run += valid ? -sp : 0.f;
;             e[k] = z + run;
;           }
;           s4[c] = make_float4(e[0], e[1], e[2], e[3]);
;         }
;         float other = __shfl_xor(run, 1);
;         float offs = m_run + (half == 0 ? other : 0.f);
; #pragma unroll 2
;         for (int s8 = 0; s8 < 4; ++s8) {
;           float4 va = s4[2 * s8], vb = s4[2 * s8 + 1];
;           float e[8] = {va.x, va.y, va.z, va.w, vb.x, vb.y, vb.z, vb.w};
;           float pv[8];
; #pragma unroll
;           for (int k = 0; k < 8; ++k) {
;             bool valid = (kpb + s8 * 8 + k) < qpos;
;             pv[k] = valid ? __builtin_amdgcn_exp2f(e[k] + offs) : 0.f;
;           }
;           uint4 ov;
;           ov.x = pack2(pv[0], pv[1]); ov.y = pack2(pv[2], pv[3]);
;           ov.z = pack2(pv[4], pv[5]); ov.w = pack2(pv[6], pv[7]);
;           *reinterpret_cast<uint4*>(prow + s8 * 16) = ov;
;         }
.LBB0_526:
	ds_read_b128 v[150:153], v148 offset:16
	ds_read_b128 v[176:179], v148
	v_add_u32_e32 v149, s54, v173
	v_add_u32_e32 v182, 0x3fdd, v149
	v_cmp_lt_i32_e32 vcc, v182, v144
	s_waitcnt lgkmcnt(1)
	v_exp_f32_e64 v175, -|v151|
	v_exp_f32_e64 v184, -|v150|
	v_max_f32_e32 v183, 0, v151
	v_add_f32_e32 v175, 1.0, v175
	v_log_f32_e32 v175, v175
	v_add_f32_e32 v182, 1.0, v184
	v_exp_f32_e64 v184, -|v153|
	v_add_u32_e32 v147, 0x3fdc, v149
	v_add_f32_e32 v175, v183, v175
	v_log_f32_e32 v182, v182
	v_cndmask_b32_e64 v175, 0, -v175, vcc
	v_cmp_lt_i32_e32 vcc, v147, v144
	v_add_f32_e32 v147, 1.0, v184
	v_exp_f32_e64 v184, -|v152|
	v_log_f32_e32 v147, v147
	v_max_f32_e32 v183, 0, v150
	v_add_u32_e32 v180, 0x3fdf, v149
	v_add_f32_e32 v182, v183, v182
	v_cndmask_b32_e64 v182, 0, -v182, vcc
	v_max_f32_e32 v183, 0, v153
	v_cmp_lt_i32_e32 vcc, v180, v144
	v_add_f32_e32 v180, 1.0, v184
	v_add_f32_e32 v147, v183, v147
	v_log_f32_e32 v180, v180
	v_cndmask_b32_e64 v147, 0, -v147, vcc
	v_add_f32_e32 v147, v146, v147
	v_add_u32_e32 v181, 0x3fde, v149
	v_max_f32_e32 v146, 0, v152
	v_add_f32_e32 v146, v146, v180
	v_cmp_lt_i32_e32 vcc, v181, v144
	s_add_i32 s54, s54, -8
	s_cmpk_eq_i32 s54, 0xffe0
	v_cndmask_b32_e64 v146, 0, -v146, vcc
	v_add_f32_e32 v146, v146, v147
	v_pk_add_f32 v[152:153], v[152:153], v[146:147]
	v_add_f32_e32 v147, v175, v146
	v_add_f32_e32 v146, v182, v147
	v_pk_add_f32 v[150:151], v[150:151], v[146:147]
	ds_write_b128 v148, v[150:153] offset:16
	s_waitcnt lgkmcnt(1)
	v_exp_f32_e64 v150, -|v177|
	v_exp_f32_e64 v175, -|v176|
	v_add_u32_e32 v147, 0x3fd8, v149
	v_add_f32_e32 v150, 1.0, v150
	v_log_f32_e32 v150, v150
	v_add_u32_e32 v151, 0x3fdb, v149
	v_add_u32_e32 v152, 0x3fda, v149
	v_add_u32_e32 v149, 0x3fd9, v149
	v_max_f32_e32 v153, 0, v177
	v_add_f32_e32 v150, v153, v150
	v_cmp_lt_i32_e32 vcc, v149, v144
	v_max_f32_e32 v153, 0, v176
	s_nop 0
	v_cndmask_b32_e64 v149, 0, -v150, vcc
	v_add_f32_e32 v150, 1.0, v175
	v_exp_f32_e64 v175, -|v179|
	v_log_f32_e32 v150, v150
	v_cmp_lt_i32_e32 vcc, v147, v144
	v_add_f32_e32 v147, 1.0, v175
	v_exp_f32_e64 v175, -|v178|
	v_log_f32_e32 v147, v147
	v_add_f32_e32 v150, v153, v150
	v_cndmask_b32_e64 v150, 0, -v150, vcc
	v_max_f32_e32 v153, 0, v179
	v_cmp_lt_i32_e32 vcc, v151, v144
	v_add_f32_e32 v151, 1.0, v175
	v_add_f32_e32 v147, v153, v147
	v_log_f32_e32 v151, v151
	v_cndmask_b32_e64 v147, 0, -v147, vcc
	v_add_f32_e32 v147, v146, v147
	v_max_f32_e32 v146, 0, v178
	v_add_f32_e32 v146, v146, v151
	v_cmp_lt_i32_e32 vcc, v152, v144
	s_nop 1
	v_cndmask_b32_e64 v146, 0, -v146, vcc
	v_add_f32_e32 v146, v146, v147
	v_pk_add_f32 v[152:153], v[178:179], v[146:147]
	v_add_f32_e32 v147, v149, v146
	v_add_f32_e32 v146, v150, v147
	v_pk_add_f32 v[150:151], v[176:177], v[146:147]
	ds_write_b128 v148, v[150:153]
	v_subrev_u32_e32 v148, 32, v148
	s_cbranch_scc0 .LBB0_526
	ds_bpermute_b32 v147, v163, v146
	s_mov_b32 s88, 0
	v_mov_b32_e32 v175, v168
	v_mov_b32_e32 v177, v167
	s_waitcnt lgkmcnt(0)
	v_cndmask_b32_e64 v148, 0, v147, s[14:15]
	v_add_f32_e32 v176, v174, v148
	s_branch .LBB0_529
.LBB0_528:
	s_or_b64 exec, exec, s[54:55]
	s_waitcnt lgkmcnt(3)
	v_add_f32_e32 v152, v176, v152
	v_exp_f32_e32 v152, v152
	s_waitcnt lgkmcnt(1)
	v_add_f32_e32 v149, v176, v149
	v_exp_f32_e32 v149, v149
	v_add_u32_e32 v182, 0x3fc9, v178
	v_add_f32_e32 v151, v176, v151
	v_add_f32_e32 v148, v176, v148
	v_cmp_lt_i32_e32 vcc, v182, v144
	v_exp_f32_e32 v185, v151
	v_exp_f32_e32 v186, v148
	v_add_u32_e32 v148, 0x3fce, v178
	s_waitcnt lgkmcnt(0)
	v_add_f32_e32 v151, v176, v180
	v_cndmask_b32_e32 v152, 0, v152, vcc
	v_exp_f32_e32 v151, v151
	v_cmp_lt_i32_e32 vcc, v148, v144
	v_add_u32_e32 v148, 0x3fcf, v178
	v_add_f32_e32 v153, v176, v153
	v_cndmask_b32_e32 v149, 0, v149, vcc
	v_cmp_lt_i32_e32 vcc, v148, v144
	v_cvt_pk_bf16_f32 v148, 0, v179
	v_exp_f32_e32 v153, v153
	v_lshrrev_b32_e32 v148, 16, v148
	v_cvt_pk_bf16_f32 v152, 0, v152
	v_add_f32_e32 v150, v176, v150
	v_cndmask_b32_e32 v151, 0, v151, vcc
	v_and_or_b32 v148, v152, s64, v148
	v_or_b32_e32 v182, 2, v181
	v_exp_f32_e32 v150, v150
	v_cvt_pk_bf16_f32 v149, 0, v149
	v_or_b32_e32 v183, 4, v181
	v_lshrrev_b32_e32 v149, 16, v149
	v_cvt_pk_bf16_f32 v151, 0, v151
	v_cmp_lt_i32_e32 vcc, v182, v144
	v_or_b32_e32 v184, 5, v181
	v_or_b32_e32 v181, 3, v181
	v_and_or_b32 v151, v151, s64, v149
	v_cndmask_b32_e32 v149, 0, v153, vcc
	v_cmp_lt_i32_e32 vcc, v183, v131
	v_cvt_pk_bf16_f32 v149, 0, v149
	s_nop 0
	v_cndmask_b32_e32 v152, 0, v185, vcc
	v_cmp_lt_i32_e32 vcc, v181, v144
	v_cvt_pk_bf16_f32 v152, 0, v152
	s_nop 0
	v_cndmask_b32_e32 v150, 0, v150, vcc
	v_cmp_lt_i32_e32 vcc, v184, v131
	v_cvt_pk_bf16_f32 v150, 0, v150
	s_nop 0
	v_cndmask_b32_e32 v153, 0, v186, vcc
	v_cvt_pk_bf16_f32 v153, 0, v153
	v_and_b32_e32 v153, 0xffff0000, v153
	v_and_b32_e32 v178, 0xffff0000, v150
	v_or_b32_sdwa v150, v153, v152 dst_sel:DWORD dst_unused:UNUSED_PAD src0_sel:DWORD src1_sel:WORD_1
	v_or_b32_sdwa v149, v178, v149 dst_sel:DWORD dst_unused:UNUSED_PAD src0_sel:DWORD src1_sel:WORD_1
	s_add_i32 s88, s88, 16
	ds_write_b128 v175, v[148:151] offset:16
	v_add_u32_e32 v177, 64, v177
	s_cmp_eq_u32 s88, 32
	v_add_u32_e32 v175, 32, v175
	s_cbranch_scc1 .LBB0_534

; __device__ __forceinline__ unsigned pack2(float a, float b) { return (unsigned)f2bf(a) | ((unsigned)f2bf(b) << 16); }
; template <int DH, int MODE>
; __device__ void attn_item(const Params& p, int layer, int b, int blk, int head, char* smem) {
;     ...
; #pragma unroll 2
;         for (int s8 = 0; s8 < 4; ++s8) {
;           float4 va = s4[2 * s8], vb = s4[2 * s8 + 1];
;           float e[8] = {va.x, va.y, va.z, va.w, vb.x, vb.y, vb.z, vb.w};
;           float pv[8];
; #pragma unroll
;           for (int k = 0; k < 8; ++k) {
;             bool valid = (kpb + s8 * 8 + k) < qpos;
;             pv[k] = valid ? __builtin_amdgcn_exp2f(e[k] + offs) : 0.f;
;           }
;           uint4 ov;
;           ov.x = pack2(pv[0], pv[1]); ov.y = pack2(pv[2], pv[3]);
;           ov.z = pack2(pv[4], pv[5]); ov.w = pack2(pv[6], pv[7]);
;           *reinterpret_cast<uint4*>(prow + s8 * 16) = ov;
;         }
.LBB0_531:
	s_or_b64 exec, exec, s[54:55]
	s_waitcnt lgkmcnt(3)
	v_add_f32_e32 v152, v176, v152
	v_exp_f32_e32 v152, v152
	s_waitcnt lgkmcnt(1)
	v_add_f32_e32 v149, v176, v149
	v_exp_f32_e32 v149, v149
	v_add_u32_e32 v183, 0x3fc1, v178
	v_add_f32_e32 v151, v176, v151
	v_add_f32_e32 v148, v176, v148
	v_cmp_lt_i32_e32 vcc, v183, v144
	v_exp_f32_e32 v186, v151
	v_exp_f32_e32 v187, v148
	v_add_u32_e32 v148, 0x3fc6, v178
	s_waitcnt lgkmcnt(0)
	v_add_f32_e32 v151, v176, v180
	v_cndmask_b32_e32 v152, 0, v152, vcc
	v_exp_f32_e32 v151, v151
	v_cmp_lt_i32_e32 vcc, v148, v144
	v_add_u32_e32 v148, 0x3fc7, v178
	v_add_f32_e32 v153, v176, v153
	v_cndmask_b32_e32 v149, 0, v149, vcc
	v_cmp_lt_i32_e32 vcc, v148, v144
	v_cvt_pk_bf16_f32 v148, 0, v181
	v_exp_f32_e32 v153, v153
	v_lshrrev_b32_e32 v148, 16, v148
	v_cvt_pk_bf16_f32 v152, 0, v152
	v_add_f32_e32 v150, v176, v150
	v_cndmask_b32_e32 v151, 0, v151, vcc
	v_and_or_b32 v148, v152, s64, v148
	v_or_b32_e32 v183, 2, v182
	v_exp_f32_e32 v150, v150
	v_cvt_pk_bf16_f32 v149, 0, v149
	v_or_b32_e32 v184, 4, v182
	v_lshrrev_b32_e32 v149, 16, v149
	v_cvt_pk_bf16_f32 v151, 0, v151
	v_cmp_lt_i32_e32 vcc, v183, v144
	v_or_b32_e32 v185, 5, v182
	v_or_b32_e32 v182, 3, v182
	v_and_or_b32 v151, v151, s64, v149
	v_cndmask_b32_e32 v149, 0, v153, vcc
	v_cmp_lt_i32_e32 vcc, v184, v131
	v_cvt_pk_bf16_f32 v149, 0, v149
	s_nop 0
	v_cndmask_b32_e32 v152, 0, v186, vcc
	v_cmp_lt_i32_e32 vcc, v182, v144
	v_cvt_pk_bf16_f32 v152, 0, v152
	s_nop 0
	v_cndmask_b32_e32 v150, 0, v150, vcc
	v_cmp_lt_i32_e32 vcc, v185, v131
	v_cvt_pk_bf16_f32 v150, 0, v150
	s_nop 0
	v_cndmask_b32_e32 v153, 0, v187, vcc
	v_cvt_pk_bf16_f32 v153, 0, v153
	v_and_b32_e32 v153, 0xffff0000, v153
	v_and_b32_e32 v180, 0xffff0000, v150
	v_or_b32_sdwa v150, v153, v152 dst_sel:DWORD dst_unused:UNUSED_PAD src0_sel:DWORD src1_sel:WORD_1
	v_or_b32_sdwa v149, v180, v149 dst_sel:DWORD dst_unused:UNUSED_PAD src0_sel:DWORD src1_sel:WORD_1
	ds_write_b128 v175, v[148:151]
	ds_read2_b32 v[152:153], v177 offset0:9 offset1:10
	ds_read2_b32 v[150:151], v177 offset0:11 offset1:12
	ds_read2_b32 v[148:149], v177 offset0:13 offset1:14
	ds_read_b32 v180, v177 offset:60
	v_add_u32_e32 v181, 0x3fc8, v178
	v_cmp_lt_i32_e32 vcc, v181, v144
	s_and_saveexec_b64 s[54:55], vcc
	s_cbranch_execz .LBB0_528
	ds_read_b32 v179, v177 offset:32
	s_waitcnt lgkmcnt(0)
	v_add_f32_e32 v179, v176, v179
	v_exp_f32_e32 v179, v179
	s_branch .LBB0_528

; template <int WM, int WN>
; __device__ __forceinline__ void store_tile_bf16(const f32x4 (&acc)[WM][WN], u16* dst, int ld, char* smem) {
;   constexpr int BM = 32 * WM, BN = 32 * WN, STR = BN + 8;
;   const int tid = opaque_tid(), lane = tid & 63, wid = tid >> 6;
;   const int wr = wid >> 1, wc = wid & 1, fr = lane & 15, fq = lane >> 4;
;   u16* T = reinterpret_cast<u16*>(smem);
; #pragma unroll
;   for (int m = 0; m < WM; ++m)
; #pragma unroll
;     for (int n = 0; n < WN; ++n)
; #pragma unroll
;       for (int j = 0; j < 4; ++j)
;         T[(wr * 16 * WM + m * 16 + fq * 4 + j) * STR + wc * 16 * WN + n * 16 + fr] = f2bf(acc[m][n][j]);
;   __syncthreads();
.LBB0_578:
	v_mov_b32_e32 v1, v232
	s_waitcnt vmcnt(7)
	v_lshrrev_b32_e32 v3, 2, v1
	v_lshrrev_b32_e32 v2, 1, v1
	v_and_b32_e32 v3, 12, v3
	v_and_or_b32 v2, v2, s64, v3
	v_and_b32_e32 v3, 0x4f, v1
	v_mul_lo_u32 v2, v2, s65
	v_lshl_add_u32 v2, v3, 1, v2
	v_cvt_pk_bf16_f32 v3, 0, v65
	ds_write_b16_d16_hi v2, v3 offset:272
	v_cvt_pk_bf16_f32 v3, 0, v66
	ds_write_b16_d16_hi v2, v3 offset:544
	v_cvt_pk_bf16_f32 v3, 0, v67
	ds_write_b16_d16_hi v2, v3 offset:816
	v_cvt_pk_bf16_f32 v3, 0, v60
	ds_write_b16_d16_hi v2, v3 offset:32
	v_cvt_pk_bf16_f32 v3, 0, v61
	ds_write_b16_d16_hi v2, v3 offset:304
	v_cvt_pk_bf16_f32 v3, 0, v62
	ds_write_b16_d16_hi v2, v3 offset:576
	v_cvt_pk_bf16_f32 v3, 0, v63
	ds_write_b16_d16_hi v2, v3 offset:848
	v_cvt_pk_bf16_f32 v3, 0, v56
	ds_write_b16_d16_hi v2, v3 offset:64
	v_cvt_pk_bf16_f32 v3, 0, v57
	ds_write_b16_d16_hi v2, v3 offset:336
	v_cvt_pk_bf16_f32 v3, 0, v58
	ds_write_b16_d16_hi v2, v3 offset:608
	v_cvt_pk_bf16_f32 v3, 0, v59
	ds_write_b16_d16_hi v2, v3 offset:880
	v_cvt_pk_bf16_f32 v3, 0, v52
	ds_write_b16_d16_hi v2, v3 offset:96
	v_cvt_pk_bf16_f32 v3, 0, v53
	ds_write_b16_d16_hi v2, v3 offset:368
	v_cvt_pk_bf16_f32 v3, 0, v54
	ds_write_b16_d16_hi v2, v3 offset:640
	v_cvt_pk_bf16_f32 v3, 0, v55
	ds_write_b16_d16_hi v2, v3 offset:912
	v_cvt_pk_bf16_f32 v3, 0, v48
	ds_write_b16_d16_hi v2, v3 offset:4352
	v_cvt_pk_bf16_f32 v3, 0, v49
	ds_write_b16_d16_hi v2, v3 offset:4624
	v_cvt_pk_bf16_f32 v3, 0, v50
	ds_write_b16_d16_hi v2, v3 offset:4896
	v_cvt_pk_bf16_f32 v3, 0, v51
	ds_write_b16_d16_hi v2, v3 offset:5168
	v_cvt_pk_bf16_f32 v3, 0, v44
	ds_write_b16_d16_hi v2, v3 offset:4384
	v_cvt_pk_bf16_f32 v3, 0, v45
	ds_write_b16_d16_hi v2, v3 offset:4656
	v_cvt_pk_bf16_f32 v3, 0, v46
	ds_write_b16_d16_hi v2, v3 offset:4928
	v_cvt_pk_bf16_f32 v3, 0, v47
	ds_write_b16_d16_hi v2, v3 offset:5200
	v_cvt_pk_bf16_f32 v3, 0, v40
	ds_write_b16_d16_hi v2, v3 offset:4416
	v_cvt_pk_bf16_f32 v3, 0, v41
	ds_write_b16_d16_hi v2, v3 offset:4688
	v_cvt_pk_bf16_f32 v3, 0, v42
	ds_write_b16_d16_hi v2, v3 offset:4960
	v_cvt_pk_bf16_f32 v3, 0, v43
	ds_write_b16_d16_hi v2, v3 offset:5232
	v_cvt_pk_bf16_f32 v3, 0, v36
	ds_write_b16_d16_hi v2, v3 offset:4448
	v_cvt_pk_bf16_f32 v3, 0, v37
	ds_write_b16_d16_hi v2, v3 offset:4720
	v_cvt_pk_bf16_f32 v3, 0, v38
	ds_write_b16_d16_hi v2, v3 offset:4992
	v_cvt_pk_bf16_f32 v3, 0, v39
	ds_write_b16_d16_hi v2, v3 offset:5264
	v_cvt_pk_bf16_f32 v3, 0, v32
	ds_write_b16_d16_hi v2, v3 offset:8704
	v_cvt_pk_bf16_f32 v3, 0, v33
	ds_write_b16_d16_hi v2, v3 offset:8976
	v_cvt_pk_bf16_f32 v3, 0, v34
	ds_write_b16_d16_hi v2, v3 offset:9248
	v_cvt_pk_bf16_f32 v3, 0, v35
	ds_write_b16_d16_hi v2, v3 offset:9520
	v_cvt_pk_bf16_f32 v3, 0, v28
	ds_write_b16_d16_hi v2, v3 offset:8736
	v_cvt_pk_bf16_f32 v3, 0, v29
	ds_write_b16_d16_hi v2, v3 offset:9008
	v_cvt_pk_bf16_f32 v3, 0, v30
	ds_write_b16_d16_hi v2, v3 offset:9280
	v_cvt_pk_bf16_f32 v3, 0, v31
	ds_write_b16_d16_hi v2, v3 offset:9552
	v_cvt_pk_bf16_f32 v3, 0, v24
	ds_write_b16_d16_hi v2, v3 offset:8768
	v_cvt_pk_bf16_f32 v3, 0, v25
	ds_write_b16_d16_hi v2, v3 offset:9040
	v_cvt_pk_bf16_f32 v3, 0, v26
	ds_write_b16_d16_hi v2, v3 offset:9312
	v_cvt_pk_bf16_f32 v3, 0, v27
	ds_write_b16_d16_hi v2, v3 offset:9584
	v_cvt_pk_bf16_f32 v3, 0, v20
	ds_write_b16_d16_hi v2, v3 offset:8800
	v_cvt_pk_bf16_f32 v3, 0, v21
	ds_write_b16_d16_hi v2, v3 offset:9072
	v_cvt_pk_bf16_f32 v3, 0, v22
	ds_write_b16_d16_hi v2, v3 offset:9344
	v_cvt_pk_bf16_f32 v3, 0, v23
	ds_write_b16_d16_hi v2, v3 offset:9616
	v_cvt_pk_bf16_f32 v3, 0, v16
	ds_write_b16_d16_hi v2, v3 offset:13056
	v_cvt_pk_bf16_f32 v3, 0, v17
	ds_write_b16_d16_hi v2, v3 offset:13328
	v_cvt_pk_bf16_f32 v3, 0, v18
	ds_write_b16_d16_hi v2, v3 offset:13600
	v_cvt_pk_bf16_f32 v3, 0, v19
	ds_write_b16_d16_hi v2, v3 offset:13872
	v_cvt_pk_bf16_f32 v3, 0, v12
	ds_write_b16_d16_hi v2, v3 offset:13088
	v_cvt_pk_bf16_f32 v3, 0, v13
	ds_write_b16_d16_hi v2, v3 offset:13360
	v_cvt_pk_bf16_f32 v3, 0, v14
	ds_write_b16_d16_hi v2, v3 offset:13632
	v_cvt_pk_bf16_f32 v3, 0, v15
	ds_write_b16_d16_hi v2, v3 offset:13904
	v_cvt_pk_bf16_f32 v3, 0, v8
	ds_write_b16_d16_hi v2, v3 offset:13120
	v_cvt_pk_bf16_f32 v3, 0, v9
	ds_write_b16_d16_hi v2, v3 offset:13392
	v_cvt_pk_bf16_f32 v3, 0, v10
	ds_write_b16_d16_hi v2, v3 offset:13664
	v_cvt_pk_bf16_f32 v3, 0, v11
	ds_write_b16_d16_hi v2, v3 offset:13936
	v_cvt_pk_bf16_f32 v3, 0, v4
	ds_write_b16_d16_hi v2, v3 offset:13152
	v_cvt_pk_bf16_f32 v3, 0, v5
	ds_write_b16_d16_hi v2, v3 offset:13424
	v_cvt_pk_bf16_f32 v3, 0, v6
	ds_write_b16_d16_hi v2, v3 offset:13696
	v_cvt_pk_bf16_f32 v64, 0, v64
	v_cvt_pk_bf16_f32 v3, 0, v7
	ds_write_b16_d16_hi v2, v64
	ds_write_b16_d16_hi v2, v3 offset:13968
	v_ashrrev_i32_e32 v2, 31, v1
	s_lshl_b64 s[12:13], s[24:25], 1
	v_lshrrev_b32_e32 v2, 28, v2
	s_add_u32 s14, s51, s12
	v_add_u32_e32 v2, v1, v2
	s_addc_u32 s15, s52, s13
	s_lshl_b64 s[12:13], s[36:37], 1
	v_ashrrev_i32_e32 v6, 4, v2
	v_and_b32_e32 v2, -16, v2
	s_add_u32 s12, s14, s12
	v_sub_u32_e32 v2, v1, v2
	v_ashrrev_i32_e32 v7, 31, v6
	s_addc_u32 s13, s15, s13
	v_mul_lo_u32 v3, v6, s65
	v_lshlrev_b32_e32 v8, 3, v2
	v_lshlrev_b64 v[6:7], 11, v[6:7]
	v_ashrrev_i32_e32 v9, 31, v8
	v_lshl_add_u64 v[6:7], s[12:13], 0, v[6:7]
	v_lshl_add_u64 v[10:11], v[8:9], 1, v[6:7]
	v_add_u32_e32 v6, 0x100, v1
	v_ashrrev_i32_e32 v7, 31, v6
	v_lshl_add_u32 v2, v2, 4, v3
	v_lshrrev_b32_e32 v7, 28, v7
	s_waitcnt lgkmcnt(0)
	s_barrier
; template <int WM, int WN>
; __device__ __forceinline__ void store_tile_bf16(const f32x4 (&acc)[WM][WN], u16* dst, int ld, char* smem) {
;     ...
;   constexpr int CPR = BN / 8;
; #pragma unroll
;   for (int i = 0; i < BM * CPR / 256; ++i) {
;     int q = tid + 256 * i, row = q / CPR, c = q % CPR;
;     uint4 v = *reinterpret_cast<const uint4*>(T + row * STR + c * 8);
;     *reinterpret_cast<uint4*>(dst + (size_t)row * ld + c * 8) = v;
;   }
	ds_read_b128 v[2:5], v2
	v_add_u32_e32 v7, v6, v7
	v_ashrrev_i32_e32 v12, 4, v7
	v_and_b32_e32 v7, -16, v7
	v_sub_u32_e32 v13, v6, v7
	v_mul_lo_u32 v6, v12, s65
	v_lshl_add_u32 v6, v13, 4, v6
	ds_read_b128 v[6:9], v6
	s_waitcnt lgkmcnt(1)
	global_store_dwordx4 v[10:11], v[2:5], off
	s_add_i32 s66, s66, s61
	s_cmp_lt_i32 s66, s62
	v_lshlrev_b32_e32 v2, 3, v13
	v_ashrrev_i32_e32 v13, 31, v12
	v_lshlrev_b64 v[4:5], 11, v[12:13]
	v_ashrrev_i32_e32 v3, 31, v2
	v_lshl_add_u64 v[4:5], s[12:13], 0, v[4:5]
	v_lshl_add_u64 v[2:3], v[2:3], 1, v[4:5]
	s_waitcnt lgkmcnt(0)
	global_store_dwordx4 v[2:3], v[6:9], off
	v_add_u32_e32 v2, 0x200, v1
	v_ashrrev_i32_e32 v3, 31, v2
	v_lshrrev_b32_e32 v3, 28, v3
	v_add_u32_e32 v3, v2, v3
	v_ashrrev_i32_e32 v6, 4, v3
	v_and_b32_e32 v3, -16, v3
	v_sub_u32_e32 v2, v2, v3
	v_ashrrev_i32_e32 v7, 31, v6
	v_mul_lo_u32 v3, v6, s65
	v_lshlrev_b32_e32 v8, 3, v2
	v_lshlrev_b64 v[6:7], 11, v[6:7]
	v_ashrrev_i32_e32 v9, 31, v8
	v_lshl_add_u64 v[6:7], s[12:13], 0, v[6:7]
	v_lshl_add_u64 v[10:11], v[8:9], 1, v[6:7]
	v_add_u32_e32 v6, 0x300, v1
	v_ashrrev_i32_e32 v7, 31, v6
	v_lshl_add_u32 v2, v2, 4, v3
	v_lshrrev_b32_e32 v7, 28, v7
	ds_read_b128 v[2:5], v2
	v_add_u32_e32 v7, v6, v7
	v_ashrrev_i32_e32 v12, 4, v7
	v_and_b32_e32 v7, -16, v7
	v_sub_u32_e32 v13, v6, v7
	v_mul_lo_u32 v6, v12, s65
	v_lshl_add_u32 v6, v13, 4, v6
	ds_read_b128 v[6:9], v6
	s_waitcnt lgkmcnt(1)
	global_store_dwordx4 v[10:11], v[2:5], off
	s_nop 1
	v_lshlrev_b32_e32 v2, 3, v13
	v_ashrrev_i32_e32 v13, 31, v12
	v_lshlrev_b64 v[4:5], 11, v[12:13]
	v_ashrrev_i32_e32 v3, 31, v2
	v_lshl_add_u64 v[4:5], s[12:13], 0, v[4:5]
	v_lshl_add_u64 v[2:3], v[2:3], 1, v[4:5]
	s_waitcnt lgkmcnt(0)
	global_store_dwordx4 v[2:3], v[6:9], off
	v_add_u32_e32 v2, 0x400, v1
	v_ashrrev_i32_e32 v3, 31, v2
	v_lshrrev_b32_e32 v3, 28, v3
	v_add_u32_e32 v3, v2, v3
	v_ashrrev_i32_e32 v6, 4, v3
	v_and_b32_e32 v3, -16, v3
	v_sub_u32_e32 v2, v2, v3
	v_ashrrev_i32_e32 v7, 31, v6
	v_mul_lo_u32 v3, v6, s65
	v_lshlrev_b32_e32 v8, 3, v2
	v_lshlrev_b64 v[6:7], 11, v[6:7]
	v_ashrrev_i32_e32 v9, 31, v8
	v_lshl_add_u64 v[6:7], s[12:13], 0, v[6:7]
	v_lshl_add_u64 v[10:11], v[8:9], 1, v[6:7]
	v_add_u32_e32 v6, 0x500, v1
	v_ashrrev_i32_e32 v7, 31, v6
	v_lshl_add_u32 v2, v2, 4, v3
	v_lshrrev_b32_e32 v7, 28, v7
	ds_read_b128 v[2:5], v2
	v_add_u32_e32 v7, v6, v7
	v_ashrrev_i32_e32 v12, 4, v7
	v_and_b32_e32 v7, -16, v7
	v_sub_u32_e32 v13, v6, v7
	v_mul_lo_u32 v6, v12, s65
	v_lshl_add_u32 v6, v13, 4, v6
	ds_read_b128 v[6:9], v6
	s_waitcnt lgkmcnt(1)
	global_store_dwordx4 v[10:11], v[2:5], off
	s_nop 1
	v_lshlrev_b32_e32 v2, 3, v13
	v_ashrrev_i32_e32 v13, 31, v12
	v_lshlrev_b64 v[4:5], 11, v[12:13]
	v_ashrrev_i32_e32 v3, 31, v2
	v_lshl_add_u64 v[4:5], s[12:13], 0, v[4:5]
	v_lshl_add_u64 v[2:3], v[2:3], 1, v[4:5]
	s_waitcnt lgkmcnt(0)
	global_store_dwordx4 v[2:3], v[6:9], off
	v_add_u32_e32 v2, 0x600, v1
	v_ashrrev_i32_e32 v3, 31, v2
	v_lshrrev_b32_e32 v3, 28, v3
	v_add_u32_e32 v3, v2, v3
	v_ashrrev_i32_e32 v6, 4, v3
	v_and_b32_e32 v3, -16, v3
	v_sub_u32_e32 v2, v2, v3
	v_ashrrev_i32_e32 v7, 31, v6
	v_mul_lo_u32 v3, v6, s65
	v_lshlrev_b32_e32 v8, 3, v2
	v_lshlrev_b64 v[6:7], 11, v[6:7]
	v_ashrrev_i32_e32 v9, 31, v8
	v_lshl_add_u64 v[6:7], s[12:13], 0, v[6:7]
	v_add_u32_e32 v1, 0x700, v1
	v_lshl_add_u64 v[10:11], v[8:9], 1, v[6:7]
	v_ashrrev_i32_e32 v6, 31, v1
	v_lshrrev_b32_e32 v6, 28, v6
	v_lshl_add_u32 v2, v2, 4, v3
	v_add_u32_e32 v6, v1, v6
	ds_read_b128 v[2:5], v2
	v_ashrrev_i32_e32 v12, 4, v6
	v_and_b32_e32 v6, -16, v6
	v_sub_u32_e32 v1, v1, v6
	v_mul_lo_u32 v6, v12, s65
	v_lshl_add_u32 v6, v1, 4, v6
	ds_read_b128 v[6:9], v6
	v_ashrrev_i32_e32 v13, 31, v12
	s_waitcnt lgkmcnt(1)
	global_store_dwordx4 v[10:11], v[2:5], off
	s_nop 1
	v_lshlrev_b32_e32 v2, 3, v1
	v_lshlrev_b64 v[4:5], 11, v[12:13]
	v_ashrrev_i32_e32 v3, 31, v2
	v_lshl_add_u64 v[4:5], s[12:13], 0, v[4:5]
	v_lshl_add_u64 v[2:3], v[2:3], 1, v[4:5]
	s_waitcnt lgkmcnt(0)
	global_store_dwordx4 v[2:3], v[6:9], off
	s_cbranch_scc0 .LBB0_599

; __device__ void phase_merge(const Params& p, int layer, char* smem) {
;     ...
;         [&](int s) {
;           int seg = s / 48, r = s - seg * 48;
;           if (r == 31) {
; #pragma unroll
;             for (int n = 0; n < 4; ++n) {
;               float bm = bmp[seg * 1024 + n * 16];
; #pragma unroll
;               for (int m = 0; m < 4; ++m)
; #pragma unroll
;                 for (int j = 0; j < 4; ++j) {
;                   GL[((m * 4 + n) * 4 + j) * 256] = f2bf(1.f / (1.f + __expf(-(acc[m][n][j] + bm))));
;                   acc[m][n][j] = 0.f;
;                 }
;             }
.LBB0_595:
	s_cmp_eq_u32 s16, 31
	s_cbranch_scc0 .LBB0_597
	s_mul_i32 s12, s68, 0xab
	s_lshr_b32 s12, s12, 1
	s_and_b32 s22, s12, 0x7000
	v_lshl_add_u64 v[2:3], v[230:231], 0, s[22:23]
	global_load_dword v164, v[2:3], off
	global_load_dword v165, v[2:3], off offset:64
	global_load_dword v166, v[2:3], off offset:128
	global_load_dword v1, v[2:3], off offset:192
	s_waitcnt vmcnt(3)
	v_add_f32_e32 v2, v160, v164
	v_add_f32_e32 v3, v161, v164
	v_mul_f32_e32 v2, 0xbfb8aa3b, v2
	v_add_f32_e32 v167, v162, v164
	v_mul_f32_e32 v3, 0xbfb8aa3b, v3
	v_exp_f32_e32 v2, v2
	v_add_f32_e32 v168, v163, v164
	v_mul_f32_e32 v167, 0xbfb8aa3b, v167
	v_exp_f32_e32 v3, v3
	v_mul_f32_e32 v168, 0xbfb8aa3b, v168
	v_exp_f32_e32 v167, v167
	v_exp_f32_e32 v168, v168
	v_add_f32_e32 v2, 1.0, v2
	v_add_f32_e32 v3, 1.0, v3
	v_add_f32_e32 v169, v144, v164
	v_add_f32_e32 v167, 1.0, v167
	v_mul_f32_e32 v169, 0xbfb8aa3b, v169
	v_add_f32_e32 v168, 1.0, v168
	v_exp_f32_e32 v169, v169
	s_nop 0
	v_add_f32_e32 v169, 1.0, v169
	v_div_scale_f32 v174, s[12:13], 1.0, v3, 1.0
	v_div_scale_f32 v176, s[14:15], 1.0, v167, 1.0
	v_div_scale_f32 v178, s[16:17], 1.0, v168, 1.0
	v_add_f32_e32 v170, v145, v164
	s_mov_b64 vcc, s[12:13]
	v_mul_f32_e32 v170, 0xbfb8aa3b, v170
	v_rcp_f32_e32 v2, v2
	s_mov_b64 vcc, s[14:15]
	v_exp_f32_e32 v170, v170
	v_rcp_f32_e32 v3, v3
	s_mov_b64 vcc, s[16:17]
	v_div_scale_f32 v180, s[20:21], 1.0, v169, 1.0
	v_cvt_pk_bf16_f32 v2, 0, v2
	v_rcp_f32_e32 v167, v167
	ds_write_b16_d16_hi v234, v2 offset:32768
	v_cvt_pk_bf16_f32 v2, 0, v3
	v_rcp_f32_e32 v168, v168
	ds_write_b16_d16_hi v234, v2 offset:33280
	v_cvt_pk_bf16_f32 v2, 0, v167
	ds_write_b16_d16_hi v234, v2 offset:33792
	v_cvt_pk_bf16_f32 v2, 0, v168
	v_add_f32_e32 v3, 1.0, v170
	s_mov_b64 vcc, s[20:21]
	ds_write_b16_d16_hi v234, v2 offset:34304
	v_rcp_f32_e32 v2, v169
	s_nop 0
	v_cvt_pk_bf16_f32 v2, 0, v2
	ds_write_b16_d16_hi v234, v2 offset:40960
	v_add_f32_e32 v167, v146, v164
	v_mul_f32_e32 v167, 0xbfb8aa3b, v167
	v_exp_f32_e32 v167, v167
	v_rcp_f32_e32 v2, v3
	v_add_f32_e32 v3, 1.0, v167
	v_cvt_pk_bf16_f32 v2, 0, v2
	ds_write_b16_d16_hi v234, v2 offset:41472
	v_add_f32_e32 v167, v147, v164
	v_mul_f32_e32 v167, 0xbfb8aa3b, v167
	v_exp_f32_e32 v167, v167
	v_rcp_f32_e32 v2, v3
	v_add_f32_e32 v3, 1.0, v167
	v_cvt_pk_bf16_f32 v2, 0, v2
	ds_write_b16_d16_hi v234, v2 offset:41984
	v_add_f32_e32 v167, v128, v164
	v_mul_f32_e32 v167, 0xbfb8aa3b, v167
	v_exp_f32_e32 v167, v167
	v_rcp_f32_e32 v2, v3
	v_add_f32_e32 v3, 1.0, v167
	v_cvt_pk_bf16_f32 v2, 0, v2
	ds_write_b16_d16_hi v234, v2 offset:42496
	v_add_f32_e32 v167, v129, v164
	v_mul_f32_e32 v167, 0xbfb8aa3b, v167
	v_exp_f32_e32 v167, v167
	v_rcp_f32_e32 v2, v3
	v_add_f32_e32 v3, 1.0, v167
	v_cvt_pk_bf16_f32 v2, 0, v2
	ds_write_b16_d16_hi v234, v2 offset:49152
	v_add_f32_e32 v167, v130, v164
	v_mul_f32_e32 v167, 0xbfb8aa3b, v167
	v_exp_f32_e32 v167, v167
	v_rcp_f32_e32 v2, v3
	v_add_f32_e32 v3, 1.0, v167
	v_cvt_pk_bf16_f32 v2, 0, v2
	ds_write_b16_d16_hi v234, v2 offset:49664
	v_add_f32_e32 v167, v131, v164
	v_mul_f32_e32 v167, 0xbfb8aa3b, v167
	v_exp_f32_e32 v167, v167
	v_rcp_f32_e32 v2, v3
	v_add_f32_e32 v3, 1.0, v167
	v_cvt_pk_bf16_f32 v2, 0, v2
	ds_write_b16_d16_hi v234, v2 offset:50176
	v_add_f32_e32 v167, v112, v164
	v_mul_f32_e32 v167, 0xbfb8aa3b, v167
	v_exp_f32_e32 v167, v167
	v_rcp_f32_e32 v2, v3
	v_add_f32_e32 v3, 1.0, v167
	v_cvt_pk_bf16_f32 v2, 0, v2
	ds_write_b16_d16_hi v234, v2 offset:50688
	v_add_f32_e32 v167, v113, v164
	v_mul_f32_e32 v167, 0xbfb8aa3b, v167
	v_exp_f32_e32 v167, v167
	v_rcp_f32_e32 v2, v3
	v_add_f32_e32 v3, 1.0, v167
	v_cvt_pk_bf16_f32 v2, 0, v2
	ds_write_b16_d16_hi v234, v2 offset:57344
	v_add_f32_e32 v167, v114, v164
	v_mul_f32_e32 v167, 0xbfb8aa3b, v167
	v_exp_f32_e32 v167, v167
	v_rcp_f32_e32 v2, v3
	v_add_f32_e32 v3, 1.0, v167
	v_cvt_pk_bf16_f32 v2, 0, v2
	ds_write_b16_d16_hi v234, v2 offset:57856
	v_add_f32_e32 v164, v115, v164
	v_mul_f32_e32 v164, 0xbfb8aa3b, v164
	v_exp_f32_e32 v164, v164
	v_rcp_f32_e32 v2, v3
	v_add_f32_e32 v3, 1.0, v164
	v_cvt_pk_bf16_f32 v2, 0, v2
	ds_write_b16_d16_hi v234, v2 offset:58368
	s_waitcnt vmcnt(2)
	v_add_f32_e32 v164, v156, v165
	v_mul_f32_e32 v164, 0xbfb8aa3b, v164
	v_exp_f32_e32 v164, v164
	v_rcp_f32_e32 v2, v3
	v_add_f32_e32 v3, 1.0, v164
	v_cvt_pk_bf16_f32 v2, 0, v2
	ds_write_b16_d16_hi v234, v2 offset:58880
	v_add_f32_e32 v164, v157, v165
	v_mul_f32_e32 v164, 0xbfb8aa3b, v164
	v_exp_f32_e32 v164, v164
	v_rcp_f32_e32 v2, v3
	v_add_f32_e32 v3, 1.0, v164
	v_cvt_pk_bf16_f32 v2, 0, v2
	ds_write_b16_d16_hi v234, v2 offset:34816
	v_add_f32_e32 v164, v158, v165
	v_mul_f32_e32 v164, 0xbfb8aa3b, v164
	v_exp_f32_e32 v164, v164
	v_rcp_f32_e32 v2, v3
	v_add_f32_e32 v3, 1.0, v164
	v_cvt_pk_bf16_f32 v2, 0, v2
	ds_write_b16_d16_hi v234, v2 offset:35328
	v_add_f32_e32 v164, v159, v165
	v_mul_f32_e32 v164, 0xbfb8aa3b, v164
	v_exp_f32_e32 v164, v164
	v_rcp_f32_e32 v2, v3
	v_add_f32_e32 v3, 1.0, v164
	v_cvt_pk_bf16_f32 v2, 0, v2
	ds_write_b16_d16_hi v234, v2 offset:35840
	v_add_f32_e32 v164, v140, v165
	v_mul_f32_e32 v164, 0xbfb8aa3b, v164
	v_exp_f32_e32 v164, v164
	v_rcp_f32_e32 v2, v3
	v_add_f32_e32 v3, 1.0, v164
	v_cvt_pk_bf16_f32 v2, 0, v2
	ds_write_b16_d16_hi v234, v2 offset:36352
	v_add_f32_e32 v164, v141, v165
	v_mul_f32_e32 v164, 0xbfb8aa3b, v164
	v_exp_f32_e32 v164, v164
	v_rcp_f32_e32 v2, v3
	v_add_f32_e32 v3, 1.0, v164
	v_cvt_pk_bf16_f32 v2, 0, v2
	ds_write_b16_d16_hi v234, v2 offset:43008
	v_add_f32_e32 v164, v142, v165
	v_mul_f32_e32 v164, 0xbfb8aa3b, v164
	v_exp_f32_e32 v164, v164
	v_rcp_f32_e32 v2, v3
	v_add_f32_e32 v3, 1.0, v164
	v_cvt_pk_bf16_f32 v2, 0, v2
	ds_write_b16_d16_hi v234, v2 offset:43520
; __device__ void phase_merge(const Params& p, int layer, char* smem) {
;     ...
;             for (int n = 0; n < 4; ++n) {
;               float bm = bmp[seg * 1024 + n * 16];
; #pragma unroll
;               for (int m = 0; m < 4; ++m)
; #pragma unroll
;                 for (int j = 0; j < 4; ++j) {
;                   GL[((m * 4 + n) * 4 + j) * 256] = f2bf(1.f / (1.f + __expf(-(acc[m][n][j] + bm))));
;                   acc[m][n][j] = 0.f;
;                 }
;             }
	v_add_f32_e32 v164, v143, v165
	v_mul_f32_e32 v164, 0xbfb8aa3b, v164
	v_exp_f32_e32 v164, v164
	v_rcp_f32_e32 v2, v3
	v_add_f32_e32 v3, 1.0, v164
	v_cvt_pk_bf16_f32 v2, 0, v2
	ds_write_b16_d16_hi v234, v2 offset:44032
	v_add_f32_e32 v164, v124, v165
	v_mul_f32_e32 v164, 0xbfb8aa3b, v164
	v_exp_f32_e32 v164, v164
	v_rcp_f32_e32 v2, v3
	v_add_f32_e32 v3, 1.0, v164
	v_cvt_pk_bf16_f32 v2, 0, v2
	ds_write_b16_d16_hi v234, v2 offset:44544
	v_add_f32_e32 v164, v125, v165
	v_mul_f32_e32 v164, 0xbfb8aa3b, v164
	v_exp_f32_e32 v164, v164
	v_rcp_f32_e32 v2, v3
	v_add_f32_e32 v3, 1.0, v164
	v_cvt_pk_bf16_f32 v2, 0, v2
	ds_write_b16_d16_hi v234, v2 offset:51200
	v_add_f32_e32 v164, v126, v165
	v_mul_f32_e32 v164, 0xbfb8aa3b, v164
	v_exp_f32_e32 v164, v164
	v_rcp_f32_e32 v2, v3
	v_add_f32_e32 v3, 1.0, v164
	v_cvt_pk_bf16_f32 v2, 0, v2
	ds_write_b16_d16_hi v234, v2 offset:51712
	v_add_f32_e32 v164, v127, v165
	v_mul_f32_e32 v164, 0xbfb8aa3b, v164
	v_exp_f32_e32 v164, v164
	v_rcp_f32_e32 v2, v3
	v_add_f32_e32 v3, 1.0, v164
	v_cvt_pk_bf16_f32 v2, 0, v2
	ds_write_b16_d16_hi v234, v2 offset:52224
	v_add_f32_e32 v164, v108, v165
	v_mul_f32_e32 v164, 0xbfb8aa3b, v164
	v_exp_f32_e32 v164, v164
	v_rcp_f32_e32 v2, v3
	v_add_f32_e32 v3, 1.0, v164
	v_cvt_pk_bf16_f32 v2, 0, v2
	ds_write_b16_d16_hi v234, v2 offset:52736
	v_add_f32_e32 v164, v109, v165
	v_mul_f32_e32 v164, 0xbfb8aa3b, v164
	v_exp_f32_e32 v164, v164
	v_rcp_f32_e32 v2, v3
	v_add_f32_e32 v3, 1.0, v164
	v_cvt_pk_bf16_f32 v2, 0, v2
	ds_write_b16_d16_hi v234, v2 offset:59392
	v_add_f32_e32 v164, v110, v165
	v_mul_f32_e32 v164, 0xbfb8aa3b, v164
	v_exp_f32_e32 v164, v164
	v_rcp_f32_e32 v2, v3
	v_add_f32_e32 v3, 1.0, v164
	v_cvt_pk_bf16_f32 v2, 0, v2
	ds_write_b16_d16_hi v234, v2 offset:59904
	v_add_f32_e32 v164, v111, v165
	v_mul_f32_e32 v164, 0xbfb8aa3b, v164
	v_exp_f32_e32 v164, v164
	v_rcp_f32_e32 v2, v3
	v_add_f32_e32 v3, 1.0, v164
	v_cvt_pk_bf16_f32 v2, 0, v2
	ds_write_b16_d16_hi v234, v2 offset:60416
	s_waitcnt vmcnt(1)
	v_add_f32_e32 v164, v152, v166
	v_mul_f32_e32 v164, 0xbfb8aa3b, v164
	v_exp_f32_e32 v164, v164
	v_rcp_f32_e32 v2, v3
	v_add_f32_e32 v3, 1.0, v164
	v_cvt_pk_bf16_f32 v2, 0, v2
	ds_write_b16_d16_hi v234, v2 offset:60928
	v_add_f32_e32 v164, v153, v166
	v_mul_f32_e32 v164, 0xbfb8aa3b, v164
	v_exp_f32_e32 v164, v164
	v_rcp_f32_e32 v2, v3
	v_add_f32_e32 v3, 1.0, v164
	v_cvt_pk_bf16_f32 v2, 0, v2
	ds_write_b16_d16_hi v234, v2 offset:36864
	v_add_f32_e32 v164, v154, v166
	v_mul_f32_e32 v164, 0xbfb8aa3b, v164
	v_exp_f32_e32 v164, v164
	v_rcp_f32_e32 v2, v3
	v_add_f32_e32 v3, 1.0, v164
	v_cvt_pk_bf16_f32 v2, 0, v2
	ds_write_b16_d16_hi v234, v2 offset:37376
	v_add_f32_e32 v164, v155, v166
	v_mul_f32_e32 v164, 0xbfb8aa3b, v164
	v_exp_f32_e32 v164, v164
	v_rcp_f32_e32 v2, v3
	v_add_f32_e32 v3, 1.0, v164
	v_cvt_pk_bf16_f32 v2, 0, v2
	ds_write_b16_d16_hi v234, v2 offset:37888
	v_add_f32_e32 v164, v136, v166
	v_mul_f32_e32 v164, 0xbfb8aa3b, v164
	v_exp_f32_e32 v164, v164
	v_rcp_f32_e32 v2, v3
	v_add_f32_e32 v3, 1.0, v164
	v_cvt_pk_bf16_f32 v2, 0, v2
	ds_write_b16_d16_hi v234, v2 offset:38400
	v_add_f32_e32 v164, v137, v166
	v_mul_f32_e32 v164, 0xbfb8aa3b, v164
	v_exp_f32_e32 v164, v164
	v_rcp_f32_e32 v2, v3
	v_add_f32_e32 v3, 1.0, v164
	v_cvt_pk_bf16_f32 v2, 0, v2
	ds_write_b16_d16_hi v234, v2 offset:45056
	v_add_f32_e32 v164, v138, v166
	v_mul_f32_e32 v164, 0xbfb8aa3b, v164
	v_exp_f32_e32 v164, v164
	v_rcp_f32_e32 v2, v3
	v_add_f32_e32 v3, 1.0, v164
	v_cvt_pk_bf16_f32 v2, 0, v2
	ds_write_b16_d16_hi v234, v2 offset:45568
	v_add_f32_e32 v164, v139, v166
	v_mul_f32_e32 v164, 0xbfb8aa3b, v164
	v_exp_f32_e32 v164, v164
	v_rcp_f32_e32 v2, v3
	v_add_f32_e32 v3, 1.0, v164
	v_cvt_pk_bf16_f32 v2, 0, v2
	ds_write_b16_d16_hi v234, v2 offset:46080
	v_add_f32_e32 v164, v120, v166
	v_mul_f32_e32 v164, 0xbfb8aa3b, v164
	v_exp_f32_e32 v164, v164
	v_rcp_f32_e32 v2, v3
	v_add_f32_e32 v3, 1.0, v164
	v_cvt_pk_bf16_f32 v2, 0, v2
	ds_write_b16_d16_hi v234, v2 offset:46592
	v_add_f32_e32 v164, v121, v166
	v_mul_f32_e32 v164, 0xbfb8aa3b, v164
	v_exp_f32_e32 v164, v164
	v_rcp_f32_e32 v2, v3
	v_add_f32_e32 v3, 1.0, v164
	v_cvt_pk_bf16_f32 v2, 0, v2
	ds_write_b16_d16_hi v234, v2 offset:53248
	v_add_f32_e32 v164, v122, v166
	v_mul_f32_e32 v164, 0xbfb8aa3b, v164
	v_exp_f32_e32 v164, v164
	v_rcp_f32_e32 v2, v3
	v_add_f32_e32 v3, 1.0, v164
	v_cvt_pk_bf16_f32 v2, 0, v2
	ds_write_b16_d16_hi v234, v2 offset:53760
	v_add_f32_e32 v164, v123, v166
	v_mul_f32_e32 v164, 0xbfb8aa3b, v164
	v_exp_f32_e32 v164, v164
	v_rcp_f32_e32 v2, v3
	v_add_f32_e32 v3, 1.0, v164
	v_cvt_pk_bf16_f32 v2, 0, v2
	ds_write_b16_d16_hi v234, v2 offset:54272
	v_add_f32_e32 v164, v100, v166
	v_mul_f32_e32 v164, 0xbfb8aa3b, v164
	v_exp_f32_e32 v164, v164
	v_rcp_f32_e32 v2, v3
	v_add_f32_e32 v3, 1.0, v164
	v_cvt_pk_bf16_f32 v2, 0, v2
	ds_write_b16_d16_hi v234, v2 offset:54784
	v_add_f32_e32 v164, v101, v166
	v_mul_f32_e32 v164, 0xbfb8aa3b, v164
	v_exp_f32_e32 v164, v164
	v_rcp_f32_e32 v2, v3
	v_add_f32_e32 v3, 1.0, v164
	v_cvt_pk_bf16_f32 v2, 0, v2
	ds_write_b16_d16_hi v234, v2 offset:61440
	v_add_f32_e32 v164, v102, v166
	v_mul_f32_e32 v164, 0xbfb8aa3b, v164
	v_exp_f32_e32 v164, v164
	v_rcp_f32_e32 v2, v3
	v_add_f32_e32 v3, 1.0, v164
	v_cvt_pk_bf16_f32 v2, 0, v2
	ds_write_b16_d16_hi v234, v2 offset:61952
	v_add_f32_e32 v164, v103, v166
	v_mul_f32_e32 v164, 0xbfb8aa3b, v164
	v_exp_f32_e32 v164, v164
	v_rcp_f32_e32 v2, v3
	v_add_f32_e32 v3, 1.0, v164
	v_cvt_pk_bf16_f32 v2, 0, v2
	ds_write_b16_d16_hi v234, v2 offset:62464
	s_waitcnt vmcnt(0)
; __device__ void phase_merge(const Params& p, int layer, char* smem) {
;     ...
;             for (int n = 0; n < 4; ++n) {
;               float bm = bmp[seg * 1024 + n * 16];
; #pragma unroll
;               for (int m = 0; m < 4; ++m)
; #pragma unroll
;                 for (int j = 0; j < 4; ++j) {
;                   GL[((m * 4 + n) * 4 + j) * 256] = f2bf(1.f / (1.f + __expf(-(acc[m][n][j] + bm))));
;                   acc[m][n][j] = 0.f;
;                 }
;             }
	v_add_f32_e32 v164, v148, v1
	v_mul_f32_e32 v164, 0xbfb8aa3b, v164
	v_exp_f32_e32 v164, v164
	v_rcp_f32_e32 v2, v3
	v_add_f32_e32 v3, 1.0, v164
	v_cvt_pk_bf16_f32 v2, 0, v2
	ds_write_b16_d16_hi v234, v2 offset:62976
	v_add_f32_e32 v164, v149, v1
	v_mul_f32_e32 v164, 0xbfb8aa3b, v164
	v_exp_f32_e32 v164, v164
	v_rcp_f32_e32 v2, v3
	v_add_f32_e32 v3, 1.0, v164
	v_cvt_pk_bf16_f32 v2, 0, v2
	ds_write_b16_d16_hi v234, v2 offset:38912
	v_add_f32_e32 v164, v150, v1
	v_mul_f32_e32 v164, 0xbfb8aa3b, v164
	v_exp_f32_e32 v164, v164
	v_rcp_f32_e32 v2, v3
	v_add_f32_e32 v3, 1.0, v164
	v_cvt_pk_bf16_f32 v2, 0, v2
	ds_write_b16_d16_hi v234, v2 offset:39424
	v_add_f32_e32 v164, v151, v1
	v_mul_f32_e32 v164, 0xbfb8aa3b, v164
	v_exp_f32_e32 v164, v164
	v_rcp_f32_e32 v2, v3
	v_add_f32_e32 v3, 1.0, v164
	v_cvt_pk_bf16_f32 v2, 0, v2
	ds_write_b16_d16_hi v234, v2 offset:39936
	v_add_f32_e32 v164, v132, v1
	v_mul_f32_e32 v164, 0xbfb8aa3b, v164
	v_exp_f32_e32 v164, v164
	v_rcp_f32_e32 v2, v3
	v_add_f32_e32 v3, 1.0, v164
	v_cvt_pk_bf16_f32 v2, 0, v2
	ds_write_b16_d16_hi v234, v2 offset:40448
	v_add_f32_e32 v164, v133, v1
	v_mul_f32_e32 v164, 0xbfb8aa3b, v164
	v_exp_f32_e32 v164, v164
	v_rcp_f32_e32 v2, v3
	v_add_f32_e32 v3, 1.0, v164
	v_cvt_pk_bf16_f32 v2, 0, v2
	ds_write_b16_d16_hi v234, v2 offset:47104
	v_add_f32_e32 v164, v134, v1
	v_mul_f32_e32 v164, 0xbfb8aa3b, v164
	v_exp_f32_e32 v164, v164
	v_rcp_f32_e32 v2, v3
	v_add_f32_e32 v3, 1.0, v164
	v_cvt_pk_bf16_f32 v2, 0, v2
	ds_write_b16_d16_hi v234, v2 offset:47616
	v_add_f32_e32 v164, v135, v1
	v_mul_f32_e32 v164, 0xbfb8aa3b, v164
	v_exp_f32_e32 v164, v164
	v_rcp_f32_e32 v2, v3
	v_add_f32_e32 v3, 1.0, v164
	v_cvt_pk_bf16_f32 v2, 0, v2
	ds_write_b16_d16_hi v234, v2 offset:48128
	v_add_f32_e32 v164, v116, v1
	v_mul_f32_e32 v164, 0xbfb8aa3b, v164
	v_exp_f32_e32 v164, v164
	v_rcp_f32_e32 v2, v3
	v_add_f32_e32 v3, 1.0, v164
	v_cvt_pk_bf16_f32 v2, 0, v2
	ds_write_b16_d16_hi v234, v2 offset:48640
	v_add_f32_e32 v164, v117, v1
	v_mul_f32_e32 v164, 0xbfb8aa3b, v164
	v_exp_f32_e32 v164, v164
	v_rcp_f32_e32 v2, v3
	v_add_f32_e32 v3, 1.0, v164
	v_cvt_pk_bf16_f32 v2, 0, v2
	ds_write_b16_d16_hi v234, v2 offset:55296
	v_add_f32_e32 v164, v118, v1
	v_mul_f32_e32 v164, 0xbfb8aa3b, v164
	v_exp_f32_e32 v164, v164
	v_rcp_f32_e32 v2, v3
	v_add_f32_e32 v3, 1.0, v164
	v_cvt_pk_bf16_f32 v2, 0, v2
	ds_write_b16_d16_hi v234, v2 offset:55808
	v_add_f32_e32 v164, v119, v1
	v_mul_f32_e32 v164, 0xbfb8aa3b, v164
	v_exp_f32_e32 v164, v164
	v_rcp_f32_e32 v2, v3
	v_add_f32_e32 v3, 1.0, v164
	v_cvt_pk_bf16_f32 v2, 0, v2
	ds_write_b16_d16_hi v234, v2 offset:56320
	v_add_f32_e32 v164, v104, v1
	v_mul_f32_e32 v164, 0xbfb8aa3b, v164
	v_exp_f32_e32 v164, v164
	v_rcp_f32_e32 v2, v3
	v_add_f32_e32 v3, 1.0, v164
	v_cvt_pk_bf16_f32 v2, 0, v2
	ds_write_b16_d16_hi v234, v2 offset:56832
	v_add_f32_e32 v164, v105, v1
	v_mul_f32_e32 v164, 0xbfb8aa3b, v164
	v_exp_f32_e32 v164, v164
	v_rcp_f32_e32 v2, v3
	v_add_f32_e32 v3, 1.0, v164
	v_cvt_pk_bf16_f32 v2, 0, v2
	ds_write_b16_d16_hi v234, v2 offset:63488
	v_add_f32_e32 v164, v106, v1
	v_mul_f32_e32 v164, 0xbfb8aa3b, v164
	v_exp_f32_e32 v164, v164
	v_rcp_f32_e32 v2, v3
	v_add_f32_e32 v3, 1.0, v164
	v_cvt_pk_bf16_f32 v2, 0, v2
	ds_write_b16_d16_hi v234, v2 offset:64000
	v_add_f32_e32 v1, v107, v1
	v_mul_f32_e32 v1, 0xbfb8aa3b, v1
	v_exp_f32_e32 v1, v1
	v_rcp_f32_e32 v2, v3
	s_nop 0
	v_cvt_pk_bf16_f32 v2, 0, v2
	v_add_f32_e32 v3, 1.0, v1
	ds_write_b16_d16_hi v234, v2 offset:64512
	v_mov_b32_e32 v1, v0
	v_mov_b32_e32 v2, v0
	v_rcp_f32_e32 v3, v3
	s_nop 0
	v_cvt_pk_bf16_f32 v3, 0, v3
	ds_write_b16_d16_hi v234, v3 offset:65024
	s_mov_b64 s[12:13], -1

; template <int WM, int WN> ...
;     ...
; #pragma unroll
;   for (int n = 0; n < 4; ++n) fb0[n] = LDSF(cur + boff + n * 1024);
; #pragma unroll
;   for (int m = 0; m < 4; ++m) fa0[m] = LDSF(cur + aoff + m * 1024);
;   acc[3][0] = MFMA16(pa, pb0, acc[3][0]);
;   acc[3][1] = MFMA16(pa, pb1, acc[3][1]);
;   acc[3][2] = MFMA16(pa, pb2, acc[3][2]);
;   acc[3][3] = MFMA16(pa, pb3, acc[3][3]);
; #pragma unroll
;   for (int n = 0; n < 4; ++n) acc[0][n] = MFMA16(fa0[0], fb0[n], acc[0][n]);
; #pragma unroll
;   for (int m = 0; m < 4; ++m) fa1[m] = LDSF(cur + aoff + APAN + m * 1024);
; #pragma unroll
;   for (int n = 0; n < 4; ++n) acc[1][n] = MFMA16(fa0[1], fb0[n], acc[1][n]);
; #pragma unroll
;   for (int n = 0; n < 4; ++n) fb1[n] = LDSF(cur + boff + BPAN + n * 1024);
; #pragma unroll
;   for (int n = 0; n < 4; ++n) acc[2][n] = MFMA16(fa0[2], fb0[n], acc[2][n]);
;   *reinterpret_cast<uint4*>(nxt + wao) = a0;
;   *reinterpret_cast<uint4*>(nxt + wao + 32 * 64) = a1;
; #pragma unroll
;   for (int n = 0; n < 4; ++n) acc[3][n] = MFMA16(fa0[3], fb0[n], acc[3][n]);
;   *reinterpret_cast<uint4*>(nxt + wao + 64 * 64) = a2;
;   *reinterpret_cast<uint4*>(nxt + wao + 96 * 64) = a3;
; #pragma unroll
;   for (int n = 0; n < 4; ++n) acc[0][n] = MFMA16(fa1[0], fb1[n], acc[0][n]);
;   *reinterpret_cast<uint4*>(nxt + wbo) = b0;
;   *reinterpret_cast<uint4*>(nxt + wbo + 32 * 64) = b1;
; #pragma unroll
;   for (int n = 0; n < 4; ++n) acc[1][n] = MFMA16(fa1[1], fb1[n], acc[1][n]);
; template <int WM, int WN, typename SrcF, typename PostF>
; __device__ __forceinline__ void gemm_stream(const int nsteps, SrcF src, PostF post, f32x4 (&acc)[WM][WN], char* smem) {
;     ...
;   for (int kt = 0; kt < nsteps; kt += 2) {
;     {
;       TileSrc s = src(min(kt + 2, nsteps - 1));
;       GLOAD_TILE(xa, s.a, s.lda, ACH);
;       GLOAD_TILE(xb, s.b, s.ldb, BCH);
;     }
;     step_compute<WM, WN>(smem, smem + STAGE, acc, aoff, boff, wao, wbo, ya0, ya1, ya2, ya3, yb0, yb1, yb2, yb3, pa, pb0, pb1, pb2, pb3);
;     SB_;
;     post(kt);
;     __syncthreads();
;     {
;       TileSrc s = src(min(kt + 3, nsteps - 1));
;       GLOAD_TILE(ya, s.a, s.lda, ACH);
;       GLOAD_TILE(yb, s.b, s.ldb, BCH);
;     }
;     step_compute<WM, WN>(smem + STAGE, smem, acc, aoff, boff, wao, wbo, xa0, xa1, xa2, xa3, xb0, xb1, xb2, xb3, pa, pb0, pb1, pb2, pb3);
;     SB_;
;     post(kt + 1);
;     __syncthreads();
;   }
.LBB0_639:
	s_add_i32 s44, s13, 2
	s_add_i32 s13, s13, 4
	s_min_u32 s13, s13, 15
	s_lshl_b32 s13, s13, 7
	s_add_u32 s92, s16, s13
	s_addc_u32 s93, s17, 0
	s_add_u32 s94, s20, s13
	s_addc_u32 s95, s21, 0
	ds_read_b128 v[144:147], v124
	ds_read_b128 v[128:131], v125 offset:16512
	ds_read_b128 v[132:135], v125 offset:17536
	ds_read_b128 v[136:139], v125 offset:18560
	ds_read_b128 v[140:143], v125 offset:19584
	v_mfma_f32_16x16x32_bf16 v[64:67], v[48:51], v[64:67], v[92:95]
	v_mfma_f32_16x16x32_bf16 v[88:91], v[48:51], v[104:107], v[88:91]
	s_waitcnt vmcnt(7)
	ds_write_b128 v126, v[32:35] offset:33024
	global_load_dwordx4 v[32:35], v116, s[92:93]
	s_add_u32 s48, s16, s13
	s_addc_u32 s49, s17, 0
	v_mfma_f32_16x16x32_bf16 v[80:83], v[48:51], v[112:115], v[80:83]
	v_mfma_f32_16x16x32_bf16 v[48:51], v[48:51], v[108:111], v[56:59]
	s_waitcnt lgkmcnt(4)
	v_mfma_f32_16x16x32_bf16 v[56:59], v[144:147], v[128:131], v[100:103]
	ds_read_b128 v[92:95], v124 offset:1024
	s_waitcnt lgkmcnt(4)
	v_mfma_f32_16x16x32_bf16 v[96:99], v[144:147], v[132:135], v[96:99]
	s_waitcnt vmcnt(7)
	ds_write_b128 v126, v[20:23] offset:35072
	global_load_dwordx4 v[20:23], v118, s[92:93]
	ds_read_b128 v[100:103], v124 offset:2048
	s_waitcnt lgkmcnt(5)
	v_mfma_f32_16x16x32_bf16 v[84:87], v[144:147], v[136:139], v[84:87]
	ds_read_b128 v[104:107], v124 offset:3072
	s_waitcnt lgkmcnt(5)
	v_mfma_f32_16x16x32_bf16 v[76:79], v[144:147], v[140:143], v[76:79]
	ds_read_b128 v[108:111], v124 offset:8256
	s_waitcnt lgkmcnt(4)
	v_mfma_f32_16x16x32_bf16 v[72:75], v[92:95], v[128:131], v[72:75]
	ds_read_b128 v[112:115], v124 offset:9280
	v_mfma_f32_16x16x32_bf16 v[68:71], v[92:95], v[132:135], v[68:71]
	ds_read_b128 v[144:147], v124 offset:10304
	v_mfma_f32_16x16x32_bf16 v[60:63], v[92:95], v[136:139], v[60:63]
	s_waitcnt vmcnt(7)
	ds_write_b128 v126, v[16:19] offset:37120
	global_load_dwordx4 v[16:19], v120, s[92:93]
	ds_read_b128 v[148:151], v124 offset:11328
	v_mfma_f32_16x16x32_bf16 v[52:55], v[92:95], v[140:143], v[52:55]
	ds_read_b128 v[92:95], v125 offset:24768
	s_waitcnt lgkmcnt(7)
	v_mfma_f32_16x16x32_bf16 v[44:47], v[100:103], v[128:131], v[44:47]
	ds_read_b128 v[152:155], v125 offset:25792
	v_mfma_f32_16x16x32_bf16 v[40:43], v[100:103], v[132:135], v[40:43]
	ds_read_b128 v[156:159], v125 offset:26816
	v_mfma_f32_16x16x32_bf16 v[36:39], v[100:103], v[136:139], v[36:39]
	s_waitcnt vmcnt(7)
	ds_write_b128 v126, v[24:27] offset:39168
	global_load_dwordx4 v[24:27], v122, s[92:93]
	ds_read_b128 v[160:163], v125 offset:27840
	v_mfma_f32_16x16x32_bf16 v[28:31], v[100:103], v[140:143], v[28:31]
	s_waitcnt lgkmcnt(10)
	v_mfma_f32_16x16x32_bf16 v[64:67], v[104:107], v[128:131], v[64:67]
	v_mfma_f32_16x16x32_bf16 v[88:91], v[104:107], v[132:135], v[88:91]
	v_mfma_f32_16x16x32_bf16 v[80:83], v[104:107], v[136:139], v[80:83]
	v_mfma_f32_16x16x32_bf16 v[48:51], v[104:107], v[140:143], v[48:51]
	s_waitcnt vmcnt(7)
	ds_write_b128 v126, v[12:15] offset:49536
	global_load_dwordx4 v[12:15], v116, s[94:95]
	s_waitcnt lgkmcnt(5)
	v_mfma_f32_16x16x32_bf16 v[56:59], v[108:111], v[92:95], v[56:59]
	s_add_u32 s48, s20, s13
	s_addc_u32 s49, s21, 0
	s_waitcnt lgkmcnt(4)
	v_mfma_f32_16x16x32_bf16 v[96:99], v[108:111], v[152:155], v[96:99]
	s_min_u32 s13, s44, 12
	s_lshl_b32 s13, s13, 7
	s_waitcnt lgkmcnt(3)
	v_mfma_f32_16x16x32_bf16 v[84:87], v[108:111], v[156:159], v[84:87]
	s_waitcnt lgkmcnt(1)
	v_mfma_f32_16x16x32_bf16 v[76:79], v[108:111], v[160:163], v[76:79]
	s_waitcnt vmcnt(7)
	ds_write_b128 v126, v[8:11] offset:51584
	global_load_dwordx4 v[8:11], v118, s[94:95]
	v_mfma_f32_16x16x32_bf16 v[72:75], v[112:115], v[92:95], v[72:75]
	v_mfma_f32_16x16x32_bf16 v[68:71], v[112:115], v[152:155], v[68:71]
	v_mfma_f32_16x16x32_bf16 v[60:63], v[112:115], v[156:159], v[60:63]
	v_mfma_f32_16x16x32_bf16 v[52:55], v[112:115], v[160:163], v[52:55]
	v_mfma_f32_16x16x32_bf16 v[44:47], v[144:147], v[92:95], v[44:47]
	s_waitcnt vmcnt(7)
	ds_write_b128 v126, v[4:7] offset:53632
	global_load_dwordx4 v[4:7], v120, s[94:95]
	v_mfma_f32_16x16x32_bf16 v[40:43], v[144:147], v[152:155], v[40:43]
	s_add_u32 s48, s16, s13
	s_addc_u32 s49, s17, 0
	s_add_u32 s50, s20, s13
	v_mfma_f32_16x16x32_bf16 v[36:39], v[144:147], v[156:159], v[36:39]
	s_addc_u32 s51, s21, 0
	v_mfma_f32_16x16x32_bf16 v[28:31], v[144:147], v[160:163], v[28:31]
	v_mfma_f32_16x16x32_bf16 v[92:95], v[148:151], v[92:95], v[64:67]
	s_waitcnt vmcnt(7)
	ds_write_b128 v126, v[0:3] offset:55680
	global_load_dwordx4 v[0:3], v122, s[94:95]
	v_mfma_f32_16x16x32_bf16 v[88:91], v[148:151], v[152:155], v[88:91]
	v_mfma_f32_16x16x32_bf16 v[80:83], v[148:151], v[156:159], v[80:83]
	v_mfma_f32_16x16x32_bf16 v[100:103], v[148:151], v[160:163], v[48:51]
	s_waitcnt lgkmcnt(0)
	s_barrier
; template <int WM, int WN> ...
;     ...
; #pragma unroll
;   for (int n = 0; n < 4; ++n) fb0[n] = LDSF(cur + boff + n * 1024);
; #pragma unroll
;   for (int m = 0; m < 4; ++m) fa0[m] = LDSF(cur + aoff + m * 1024);
;   acc[3][0] = MFMA16(pa, pb0, acc[3][0]);
;   acc[3][1] = MFMA16(pa, pb1, acc[3][1]);
;   acc[3][2] = MFMA16(pa, pb2, acc[3][2]);
;   acc[3][3] = MFMA16(pa, pb3, acc[3][3]);
; #pragma unroll
;   for (int n = 0; n < 4; ++n) acc[0][n] = MFMA16(fa0[0], fb0[n], acc[0][n]);
; #pragma unroll
;   for (int m = 0; m < 4; ++m) fa1[m] = LDSF(cur + aoff + APAN + m * 1024);
; #pragma unroll
;   for (int n = 0; n < 4; ++n) acc[1][n] = MFMA16(fa0[1], fb0[n], acc[1][n]);
; #pragma unroll
;   for (int n = 0; n < 4; ++n) fb1[n] = LDSF(cur + boff + BPAN + n * 1024);
; #pragma unroll
;   for (int n = 0; n < 4; ++n) acc[2][n] = MFMA16(fa0[2], fb0[n], acc[2][n]);
;   *reinterpret_cast<uint4*>(nxt + wao) = a0;
;   *reinterpret_cast<uint4*>(nxt + wao + 32 * 64) = a1;
; #pragma unroll
;   for (int n = 0; n < 4; ++n) acc[3][n] = MFMA16(fa0[3], fb0[n], acc[3][n]);
;   *reinterpret_cast<uint4*>(nxt + wao + 64 * 64) = a2;
;   *reinterpret_cast<uint4*>(nxt + wao + 96 * 64) = a3;
; #pragma unroll
;   for (int n = 0; n < 4; ++n) acc[0][n] = MFMA16(fa1[0], fb1[n], acc[0][n]);
;   *reinterpret_cast<uint4*>(nxt + wbo) = b0;
;   *reinterpret_cast<uint4*>(nxt + wbo + 32 * 64) = b1;
; #pragma unroll
;   for (int n = 0; n < 4; ++n) acc[1][n] = MFMA16(fa1[1], fb1[n], acc[1][n]);
; template <int WM, int WN, typename SrcF, typename PostF>
; __device__ __forceinline__ void gemm_stream(const int nsteps, SrcF src, PostF post, f32x4 (&acc)[WM][WN], char* smem) {
;     ...
;   for (int kt = 0; kt < nsteps; kt += 2) {
;     {
;       TileSrc s = src(min(kt + 2, nsteps - 1));
;       GLOAD_TILE(xa, s.a, s.lda, ACH);
;       GLOAD_TILE(xb, s.b, s.ldb, BCH);
;     }
;     step_compute<WM, WN>(smem, smem + STAGE, acc, aoff, boff, wao, wbo, ya0, ya1, ya2, ya3, yb0, yb1, yb2, yb3, pa, pb0, pb1, pb2, pb3);
;     SB_;
;     post(kt);
;     __syncthreads();
;     {
;       TileSrc s = src(min(kt + 3, nsteps - 1));
;       GLOAD_TILE(ya, s.a, s.lda, ACH);
;       GLOAD_TILE(yb, s.b, s.ldb, BCH);
;     }
;     step_compute<WM, WN>(smem + STAGE, smem, acc, aoff, boff, wao, wbo, xa0, xa1, xa2, xa3, xb0, xb1, xb2, xb3, pa, pb0, pb1, pb2, pb3);
;     SB_;
;     post(kt + 1);
;     __syncthreads();
;   }
	s_nop 0
	ds_read_b128 v[48:51], v124 offset:33024
	ds_read_b128 v[108:111], v125 offset:49536
	ds_read_b128 v[128:131], v125 offset:50560
	ds_read_b128 v[132:135], v125 offset:51584
	ds_read_b128 v[136:139], v125 offset:52608
	s_waitcnt lgkmcnt(3)
	v_mfma_f32_16x16x32_bf16 v[140:143], v[48:51], v[108:111], v[56:59]
	s_waitcnt lgkmcnt(2)
	v_mfma_f32_16x16x32_bf16 v[96:99], v[48:51], v[128:131], v[96:99]
	s_waitcnt vmcnt(7)
	ds_write_b128 v126, v[32:35]
	global_load_dwordx4 v[32:35], v116, s[48:49] offset:384
	s_waitcnt lgkmcnt(2)
	v_mfma_f32_16x16x32_bf16 v[84:87], v[48:51], v[132:135], v[84:87]
	s_waitcnt lgkmcnt(0)
	v_mfma_f32_16x16x32_bf16 v[76:79], v[48:51], v[136:139], v[76:79]
	ds_read_b128 v[48:51], v124 offset:34048
	s_waitcnt lgkmcnt(0)
	v_mfma_f32_16x16x32_bf16 v[72:75], v[48:51], v[108:111], v[72:75]
	s_waitcnt vmcnt(7)
	ds_write_b128 v126, v[20:23] offset:2048
	global_load_dwordx4 v[20:23], v118, s[48:49] offset:384
	ds_read_b128 v[56:59], v124 offset:35072
	v_mfma_f32_16x16x32_bf16 v[68:71], v[48:51], v[128:131], v[68:71]
	ds_read_b128 v[144:147], v124 offset:36096
	v_mfma_f32_16x16x32_bf16 v[60:63], v[48:51], v[132:135], v[60:63]
	ds_read_b128 v[148:151], v124 offset:41280
	v_mfma_f32_16x16x32_bf16 v[52:55], v[48:51], v[136:139], v[52:55]
	ds_read_b128 v[152:155], v124 offset:42304
	s_waitcnt lgkmcnt(3)
	v_mfma_f32_16x16x32_bf16 v[44:47], v[56:59], v[108:111], v[44:47]
	s_waitcnt vmcnt(7)
	ds_write_b128 v126, v[16:19] offset:4096
	global_load_dwordx4 v[16:19], v120, s[48:49] offset:384
	ds_read_b128 v[156:159], v124 offset:43328
	v_mfma_f32_16x16x32_bf16 v[40:43], v[56:59], v[128:131], v[40:43]
	ds_read_b128 v[48:51], v124 offset:44352
	v_mfma_f32_16x16x32_bf16 v[36:39], v[56:59], v[132:135], v[36:39]
	ds_read_b128 v[64:67], v125 offset:57792
	v_mfma_f32_16x16x32_bf16 v[28:31], v[56:59], v[136:139], v[28:31]
	s_waitcnt vmcnt(7)
	ds_write_b128 v126, v[24:27] offset:6144
	global_load_dwordx4 v[24:27], v122, s[48:49] offset:384
	ds_read_b128 v[104:107], v125 offset:58816
	s_waitcnt lgkmcnt(8)
	v_mfma_f32_16x16x32_bf16 v[92:95], v[144:147], v[108:111], v[92:95]
	ds_read_b128 v[112:115], v125 offset:59840
	v_mfma_f32_16x16x32_bf16 v[88:91], v[144:147], v[128:131], v[88:91]
	ds_read_b128 v[108:111], v125 offset:60864
	v_mfma_f32_16x16x32_bf16 v[80:83], v[144:147], v[132:135], v[80:83]
	v_mfma_f32_16x16x32_bf16 v[56:59], v[144:147], v[136:139], v[100:103]
	s_waitcnt vmcnt(7)
	ds_write_b128 v126, v[12:15] offset:16512
	global_load_dwordx4 v[12:15], v116, s[50:51] offset:384
	s_waitcnt lgkmcnt(5)
	v_mfma_f32_16x16x32_bf16 v[100:103], v[148:151], v[64:67], v[140:143]
	s_waitcnt lgkmcnt(3)
	v_mfma_f32_16x16x32_bf16 v[96:99], v[148:151], v[104:107], v[96:99]
	s_waitcnt lgkmcnt(2)
	v_mfma_f32_16x16x32_bf16 v[84:87], v[148:151], v[112:115], v[84:87]
	s_waitcnt vmcnt(7)
	ds_write_b128 v126, v[8:11] offset:18560
	global_load_dwordx4 v[8:11], v118, s[50:51] offset:384
	s_waitcnt lgkmcnt(2)
	v_mfma_f32_16x16x32_bf16 v[76:79], v[148:151], v[108:111], v[76:79]
	v_mfma_f32_16x16x32_bf16 v[72:75], v[152:155], v[64:67], v[72:75]
	v_mfma_f32_16x16x32_bf16 v[68:71], v[152:155], v[104:107], v[68:71]
	v_mfma_f32_16x16x32_bf16 v[60:63], v[152:155], v[112:115], v[60:63]
	s_waitcnt vmcnt(7)
	ds_write_b128 v126, v[4:7] offset:20608
	global_load_dwordx4 v[4:7], v120, s[50:51] offset:384
	v_mfma_f32_16x16x32_bf16 v[52:55], v[152:155], v[108:111], v[52:55]
	v_mfma_f32_16x16x32_bf16 v[44:47], v[156:159], v[64:67], v[44:47]
	v_mfma_f32_16x16x32_bf16 v[40:43], v[156:159], v[104:107], v[40:43]
	s_waitcnt vmcnt(7)
	ds_write_b128 v126, v[0:3] offset:22656
	global_load_dwordx4 v[0:3], v122, s[50:51] offset:384
	v_mfma_f32_16x16x32_bf16 v[36:39], v[156:159], v[112:115], v[36:39]
	v_mfma_f32_16x16x32_bf16 v[28:31], v[156:159], v[108:111], v[28:31]
	s_cmp_lt_u32 s44, 12
	s_mov_b32 s13, s44
	s_waitcnt lgkmcnt(0)
	s_barrier
	s_cbranch_scc1 .LBB0_639
	ds_read_b128 v[144:147], v124
	ds_read_b128 v[128:131], v125 offset:16512
	ds_read_b128 v[132:135], v125 offset:17536
	ds_read_b128 v[136:139], v125 offset:18560
	ds_read_b128 v[140:143], v125 offset:19584
	v_mfma_f32_16x16x32_bf16 v[64:67], v[48:51], v[64:67], v[92:95]
	s_add_i32 s44, s13, 2
	s_add_i32 s13, s13, 4
	s_min_u32 s13, s13, 15
	v_mfma_f32_16x16x32_bf16 v[88:91], v[48:51], v[104:107], v[88:91]
	s_lshl_b32 s13, s13, 7
	s_add_u32 s48, s16, s13
	s_addc_u32 s49, s17, 0
	v_mfma_f32_16x16x32_bf16 v[80:83], v[48:51], v[112:115], v[80:83]
	v_mfma_f32_16x16x32_bf16 v[48:51], v[48:51], v[108:111], v[56:59]
	s_waitcnt lgkmcnt(3)
	v_mfma_f32_16x16x32_bf16 v[56:59], v[144:147], v[128:131], v[100:103]
	ds_read_b128 v[92:95], v124 offset:1024
	s_waitcnt lgkmcnt(3)
	v_mfma_f32_16x16x32_bf16 v[96:99], v[144:147], v[132:135], v[96:99]
	ds_read_b128 v[100:103], v124 offset:2048
	s_waitcnt lgkmcnt(3)
	v_mfma_f32_16x16x32_bf16 v[84:87], v[144:147], v[136:139], v[84:87]
	ds_read_b128 v[104:107], v124 offset:3072
	s_waitcnt lgkmcnt(3)
	v_mfma_f32_16x16x32_bf16 v[76:79], v[144:147], v[140:143], v[76:79]
	ds_read_b128 v[108:111], v124 offset:8256
	s_waitcnt lgkmcnt(3)
	v_mfma_f32_16x16x32_bf16 v[72:75], v[92:95], v[128:131], v[72:75]
	ds_read_b128 v[112:115], v124 offset:9280
	v_mfma_f32_16x16x32_bf16 v[68:71], v[92:95], v[132:135], v[68:71]
	ds_read_b128 v[144:147], v124 offset:10304
	v_mfma_f32_16x16x32_bf16 v[60:63], v[92:95], v[136:139], v[60:63]
	ds_read_b128 v[148:151], v124 offset:11328
	v_mfma_f32_16x16x32_bf16 v[52:55], v[92:95], v[140:143], v[52:55]
	ds_read_b128 v[92:95], v125 offset:24768
	s_waitcnt lgkmcnt(6)
; template <int WM, int WN> ...
;     ...
; #pragma unroll
;   for (int n = 0; n < 4; ++n) fb0[n] = LDSF(cur + boff + n * 1024);
; #pragma unroll
;   for (int m = 0; m < 4; ++m) fa0[m] = LDSF(cur + aoff + m * 1024);
;   acc[3][0] = MFMA16(pa, pb0, acc[3][0]);
;   acc[3][1] = MFMA16(pa, pb1, acc[3][1]);
;   acc[3][2] = MFMA16(pa, pb2, acc[3][2]);
;   acc[3][3] = MFMA16(pa, pb3, acc[3][3]);
; #pragma unroll
;   for (int n = 0; n < 4; ++n) acc[0][n] = MFMA16(fa0[0], fb0[n], acc[0][n]);
; #pragma unroll
;   for (int m = 0; m < 4; ++m) fa1[m] = LDSF(cur + aoff + APAN + m * 1024);
; #pragma unroll
;   for (int n = 0; n < 4; ++n) acc[1][n] = MFMA16(fa0[1], fb0[n], acc[1][n]);
; #pragma unroll
;   for (int n = 0; n < 4; ++n) fb1[n] = LDSF(cur + boff + BPAN + n * 1024);
; #pragma unroll
;   for (int n = 0; n < 4; ++n) acc[2][n] = MFMA16(fa0[2], fb0[n], acc[2][n]);
;   *reinterpret_cast<uint4*>(nxt + wao) = a0;
;   *reinterpret_cast<uint4*>(nxt + wao + 32 * 64) = a1;
; #pragma unroll
;   for (int n = 0; n < 4; ++n) acc[3][n] = MFMA16(fa0[3], fb0[n], acc[3][n]);
;   *reinterpret_cast<uint4*>(nxt + wao + 64 * 64) = a2;
;   *reinterpret_cast<uint4*>(nxt + wao + 96 * 64) = a3;
; #pragma unroll
;   for (int n = 0; n < 4; ++n) acc[0][n] = MFMA16(fa1[0], fb1[n], acc[0][n]);
;   *reinterpret_cast<uint4*>(nxt + wbo) = b0;
;   *reinterpret_cast<uint4*>(nxt + wbo + 32 * 64) = b1;
; #pragma unroll
;   for (int n = 0; n < 4; ++n) acc[1][n] = MFMA16(fa1[1], fb1[n], acc[1][n]);
; template <int WM, int WN, typename SrcF, typename PostF>
; __device__ __forceinline__ void gemm_stream(const int nsteps, SrcF src, PostF post, f32x4 (&acc)[WM][WN], char* smem) {
;     ...
;   for (int kt = 0; kt < nsteps; kt += 2) {
;     {
;       TileSrc s = src(min(kt + 2, nsteps - 1));
;       GLOAD_TILE(xa, s.a, s.lda, ACH);
;       GLOAD_TILE(xb, s.b, s.ldb, BCH);
;     }
;     step_compute<WM, WN>(smem, smem + STAGE, acc, aoff, boff, wao, wbo, ya0, ya1, ya2, ya3, yb0, yb1, yb2, yb3, pa, pb0, pb1, pb2, pb3);
;     SB_;
;     post(kt);
;     __syncthreads();
;     {
;       TileSrc s = src(min(kt + 3, nsteps - 1));
;       GLOAD_TILE(ya, s.a, s.lda, ACH);
;       GLOAD_TILE(yb, s.b, s.ldb, BCH);
;     }
;     step_compute<WM, WN>(smem + STAGE, smem, acc, aoff, boff, wao, wbo, xa0, xa1, xa2, xa3, xb0, xb1, xb2, xb3, pa, pb0, pb1, pb2, pb3);
;     SB_;
;     post(kt + 1);
;     __syncthreads();
;   }
	v_mfma_f32_16x16x32_bf16 v[44:47], v[100:103], v[128:131], v[44:47]
	ds_read_b128 v[152:155], v125 offset:25792
	v_mfma_f32_16x16x32_bf16 v[40:43], v[100:103], v[132:135], v[40:43]
	ds_read_b128 v[156:159], v125 offset:26816
	v_mfma_f32_16x16x32_bf16 v[36:39], v[100:103], v[136:139], v[36:39]
	ds_read_b128 v[160:163], v125 offset:27840
	v_mfma_f32_16x16x32_bf16 v[28:31], v[100:103], v[140:143], v[28:31]
	s_waitcnt lgkmcnt(8)
	v_mfma_f32_16x16x32_bf16 v[64:67], v[104:107], v[128:131], v[64:67]
	s_waitcnt vmcnt(7)
	ds_write_b128 v126, v[32:35] offset:33024
	v_mfma_f32_16x16x32_bf16 v[88:91], v[104:107], v[132:135], v[88:91]
	v_mfma_f32_16x16x32_bf16 v[80:83], v[104:107], v[136:139], v[80:83]
	s_waitcnt vmcnt(6)
	ds_write_b128 v126, v[20:23] offset:35072
	v_mfma_f32_16x16x32_bf16 v[48:51], v[104:107], v[140:143], v[48:51]
	s_waitcnt lgkmcnt(5)
	v_mfma_f32_16x16x32_bf16 v[56:59], v[108:111], v[92:95], v[56:59]
	s_waitcnt vmcnt(5)
	ds_write_b128 v126, v[16:19] offset:37120
	s_add_u32 s48, s20, s13
	s_addc_u32 s49, s21, 0
	s_waitcnt lgkmcnt(5)
	v_mfma_f32_16x16x32_bf16 v[96:99], v[108:111], v[152:155], v[96:99]
	s_min_u32 s13, s44, 12
	s_lshl_b32 s13, s13, 7
	s_waitcnt lgkmcnt(4)
	v_mfma_f32_16x16x32_bf16 v[84:87], v[108:111], v[156:159], v[84:87]
	s_waitcnt vmcnt(4)
	ds_write_b128 v126, v[24:27] offset:39168
	s_waitcnt lgkmcnt(4)
	v_mfma_f32_16x16x32_bf16 v[76:79], v[108:111], v[160:163], v[76:79]
	v_mfma_f32_16x16x32_bf16 v[72:75], v[112:115], v[92:95], v[72:75]
	s_waitcnt vmcnt(3)
	ds_write_b128 v126, v[12:15] offset:49536
	v_mfma_f32_16x16x32_bf16 v[68:71], v[112:115], v[152:155], v[68:71]
	v_mfma_f32_16x16x32_bf16 v[60:63], v[112:115], v[156:159], v[60:63]
	s_waitcnt vmcnt(2)
	ds_write_b128 v126, v[8:11] offset:51584
	v_mfma_f32_16x16x32_bf16 v[52:55], v[112:115], v[160:163], v[52:55]
	v_mfma_f32_16x16x32_bf16 v[44:47], v[144:147], v[92:95], v[44:47]
	s_waitcnt vmcnt(1)
	ds_write_b128 v126, v[4:7] offset:53632
	v_mfma_f32_16x16x32_bf16 v[40:43], v[144:147], v[152:155], v[40:43]
	s_add_u32 s48, s16, s13
	s_addc_u32 s49, s17, 0
	s_add_u32 s50, s20, s13
	v_mfma_f32_16x16x32_bf16 v[36:39], v[144:147], v[156:159], v[36:39]
	s_waitcnt vmcnt(0)
	ds_write_b128 v126, v[0:3] offset:55680
	s_addc_u32 s51, s21, 0
	v_mfma_f32_16x16x32_bf16 v[28:31], v[144:147], v[160:163], v[28:31]
	v_mfma_f32_16x16x32_bf16 v[92:95], v[148:151], v[92:95], v[64:67]
	v_mfma_f32_16x16x32_bf16 v[88:91], v[148:151], v[152:155], v[88:91]
	v_mfma_f32_16x16x32_bf16 v[80:83], v[148:151], v[156:159], v[80:83]
	v_mfma_f32_16x16x32_bf16 v[100:103], v[148:151], v[160:163], v[48:51]
	s_waitcnt lgkmcnt(0)
	s_barrier
	s_nop 0
	ds_read_b128 v[48:51], v124 offset:33024
	ds_read_b128 v[108:111], v125 offset:49536
	ds_read_b128 v[128:131], v125 offset:50560
	ds_read_b128 v[132:135], v125 offset:51584
	ds_read_b128 v[136:139], v125 offset:52608
	s_waitcnt lgkmcnt(3)
	v_mfma_f32_16x16x32_bf16 v[140:143], v[48:51], v[108:111], v[56:59]
	s_waitcnt lgkmcnt(2)
	v_mfma_f32_16x16x32_bf16 v[96:99], v[48:51], v[128:131], v[96:99]
	s_waitcnt lgkmcnt(1)
	v_mfma_f32_16x16x32_bf16 v[84:87], v[48:51], v[132:135], v[84:87]
	s_waitcnt lgkmcnt(0)
	v_mfma_f32_16x16x32_bf16 v[76:79], v[48:51], v[136:139], v[76:79]
	ds_read_b128 v[48:51], v124 offset:34048
	s_waitcnt lgkmcnt(0)
	v_mfma_f32_16x16x32_bf16 v[72:75], v[48:51], v[108:111], v[72:75]
	ds_read_b128 v[56:59], v124 offset:35072
	v_mfma_f32_16x16x32_bf16 v[68:71], v[48:51], v[128:131], v[68:71]
	ds_read_b128 v[144:147], v124 offset:36096
	v_mfma_f32_16x16x32_bf16 v[60:63], v[48:51], v[132:135], v[60:63]
	ds_read_b128 v[148:151], v124 offset:41280
	v_mfma_f32_16x16x32_bf16 v[52:55], v[48:51], v[136:139], v[52:55]
	ds_read_b128 v[152:155], v124 offset:42304
	s_waitcnt lgkmcnt(3)
	v_mfma_f32_16x16x32_bf16 v[44:47], v[56:59], v[108:111], v[44:47]
	ds_read_b128 v[156:159], v124 offset:43328
	v_mfma_f32_16x16x32_bf16 v[40:43], v[56:59], v[128:131], v[40:43]
	ds_read_b128 v[48:51], v124 offset:44352
	v_mfma_f32_16x16x32_bf16 v[36:39], v[56:59], v[132:135], v[36:39]
	ds_read_b128 v[64:67], v125 offset:57792
	v_mfma_f32_16x16x32_bf16 v[28:31], v[56:59], v[136:139], v[28:31]
	ds_read_b128 v[104:107], v125 offset:58816
	s_waitcnt lgkmcnt(6)
	v_mfma_f32_16x16x32_bf16 v[92:95], v[144:147], v[108:111], v[92:95]
	ds_read_b128 v[112:115], v125 offset:59840
	v_mfma_f32_16x16x32_bf16 v[88:91], v[144:147], v[128:131], v[88:91]
	ds_read_b128 v[108:111], v125 offset:60864
	v_mfma_f32_16x16x32_bf16 v[80:83], v[144:147], v[132:135], v[80:83]
	v_mfma_f32_16x16x32_bf16 v[56:59], v[144:147], v[136:139], v[100:103]
	ds_write_b128 v126, v[32:35]
	s_waitcnt lgkmcnt(4)
	v_mfma_f32_16x16x32_bf16 v[100:103], v[148:151], v[64:67], v[140:143]
	s_waitcnt lgkmcnt(3)
	v_mfma_f32_16x16x32_bf16 v[96:99], v[148:151], v[104:107], v[96:99]
	ds_write_b128 v126, v[20:23] offset:2048
	s_waitcnt lgkmcnt(3)
	v_mfma_f32_16x16x32_bf16 v[84:87], v[148:151], v[112:115], v[84:87]
	s_waitcnt lgkmcnt(2)
	v_mfma_f32_16x16x32_bf16 v[76:79], v[148:151], v[108:111], v[76:79]
	ds_write_b128 v126, v[16:19] offset:4096
	v_mfma_f32_16x16x32_bf16 v[72:75], v[152:155], v[64:67], v[72:75]
	v_mfma_f32_16x16x32_bf16 v[68:71], v[152:155], v[104:107], v[68:71]
	ds_write_b128 v126, v[24:27] offset:6144
	v_mfma_f32_16x16x32_bf16 v[60:63], v[152:155], v[112:115], v[60:63]
	v_mfma_f32_16x16x32_bf16 v[52:55], v[152:155], v[108:111], v[52:55]
	ds_write_b128 v126, v[12:15] offset:16512
	v_mfma_f32_16x16x32_bf16 v[44:47], v[156:159], v[64:67], v[44:47]
	v_mfma_f32_16x16x32_bf16 v[40:43], v[156:159], v[104:107], v[40:43]
	ds_write_b128 v126, v[8:11] offset:18560
	v_mfma_f32_16x16x32_bf16 v[36:39], v[156:159], v[112:115], v[36:39]
	v_mfma_f32_16x16x32_bf16 v[28:31], v[156:159], v[108:111], v[28:31]
	ds_write_b128 v126, v[4:7] offset:20608
	ds_write_b128 v126, v[0:3] offset:22656
	s_cmp_lt_u32 s44, 14
	s_mov_b32 s13, s44
	s_waitcnt lgkmcnt(0)
	s_barrier
; #define MFMA16(a, b, c) __builtin_amdgcn_mfma_f32_16x16x32_bf16(a, b, c, 0, 0, 0)
; template <int WM, int WN, typename SrcF, typename PostF>
; __device__ __forceinline__ void gemm_stream(const int nsteps, SrcF src, PostF post, f32x4 (&acc)[WM][WN], char* smem) {
;     ...
;   acc[3][0] = MFMA16(pa, pb0, acc[3][0]);
;   acc[3][1] = MFMA16(pa, pb1, acc[3][1]);
;   acc[3][2] = MFMA16(pa, pb2, acc[3][2]);
;   acc[3][3] = MFMA16(pa, pb3, acc[3][3]);
; template <int WM, int WN>
; __device__ __forceinline__ void store_tile_bf16(const f32x4 (&acc)[WM][WN], u16* dst, int ld, char* smem) {
;     ...
;   u16* T = reinterpret_cast<u16*>(smem);
; #pragma unroll
;   for (int m = 0; m < WM; ++m)
; #pragma unroll
;     for (int n = 0; n < WN; ++n)
; #pragma unroll
;       for (int j = 0; j < 4; ++j)
;         T[(wr * 16 * WM + m * 16 + fq * 4 + j) * STR + wc * 16 * WN + n * 16 + fr] = f2bf(acc[m][n][j]);
;   __syncthreads();
	s_waitcnt vmcnt(5)
	v_mov_b32_e32 v16, v232
	s_waitcnt vmcnt(0)
	v_mfma_f32_16x16x32_bf16 v[0:3], v[48:51], v[64:67], v[92:95]
	v_lshrrev_b32_e32 v18, 2, v16
	v_lshrrev_b32_e32 v17, 1, v16
	v_and_b32_e32 v18, 12, v18
	v_and_or_b32 v17, v17, s40, v18
	v_and_b32_e32 v18, 0x4f, v16
	v_mul_lo_u32 v17, v17, s42
	v_lshl_add_u32 v17, v18, 1, v17
	v_cvt_pk_bf16_f32 v18, 0, v101
	ds_write_b16_d16_hi v17, v18 offset:272
	v_cvt_pk_bf16_f32 v18, 0, v102
	ds_write_b16_d16_hi v17, v18 offset:544
	v_cvt_pk_bf16_f32 v18, 0, v103
	ds_write_b16_d16_hi v17, v18 offset:816
	v_cvt_pk_bf16_f32 v18, 0, v96
	ds_write_b16_d16_hi v17, v18 offset:32
	v_cvt_pk_bf16_f32 v18, 0, v97
	ds_write_b16_d16_hi v17, v18 offset:304
	v_cvt_pk_bf16_f32 v18, 0, v98
	ds_write_b16_d16_hi v17, v18 offset:576
	v_cvt_pk_bf16_f32 v18, 0, v99
	ds_write_b16_d16_hi v17, v18 offset:848
	v_cvt_pk_bf16_f32 v18, 0, v84
	ds_write_b16_d16_hi v17, v18 offset:64
	v_cvt_pk_bf16_f32 v18, 0, v85
	ds_write_b16_d16_hi v17, v18 offset:336
	v_cvt_pk_bf16_f32 v18, 0, v86
	ds_write_b16_d16_hi v17, v18 offset:608
	v_cvt_pk_bf16_f32 v18, 0, v87
	ds_write_b16_d16_hi v17, v18 offset:880
	v_cvt_pk_bf16_f32 v18, 0, v76
	ds_write_b16_d16_hi v17, v18 offset:96
	v_cvt_pk_bf16_f32 v18, 0, v77
	ds_write_b16_d16_hi v17, v18 offset:368
	v_cvt_pk_bf16_f32 v18, 0, v78
	ds_write_b16_d16_hi v17, v18 offset:640
	v_cvt_pk_bf16_f32 v18, 0, v79
	ds_write_b16_d16_hi v17, v18 offset:912
	v_cvt_pk_bf16_f32 v18, 0, v72
	ds_write_b16_d16_hi v17, v18 offset:4352
	v_cvt_pk_bf16_f32 v18, 0, v73
	ds_write_b16_d16_hi v17, v18 offset:4624
	v_cvt_pk_bf16_f32 v18, 0, v74
	ds_write_b16_d16_hi v17, v18 offset:4896
	v_cvt_pk_bf16_f32 v18, 0, v75
	ds_write_b16_d16_hi v17, v18 offset:5168
	v_cvt_pk_bf16_f32 v18, 0, v68
	ds_write_b16_d16_hi v17, v18 offset:4384
	v_cvt_pk_bf16_f32 v18, 0, v69
	ds_write_b16_d16_hi v17, v18 offset:4656
	v_cvt_pk_bf16_f32 v18, 0, v70
	ds_write_b16_d16_hi v17, v18 offset:4928
	v_cvt_pk_bf16_f32 v18, 0, v71
	ds_write_b16_d16_hi v17, v18 offset:5200
	v_cvt_pk_bf16_f32 v18, 0, v60
	ds_write_b16_d16_hi v17, v18 offset:4416
	v_cvt_pk_bf16_f32 v18, 0, v61
	ds_write_b16_d16_hi v17, v18 offset:4688
	v_cvt_pk_bf16_f32 v18, 0, v62
	ds_write_b16_d16_hi v17, v18 offset:4960
	v_cvt_pk_bf16_f32 v18, 0, v63
	ds_write_b16_d16_hi v17, v18 offset:5232
	v_cvt_pk_bf16_f32 v18, 0, v52
	ds_write_b16_d16_hi v17, v18 offset:4448
	v_cvt_pk_bf16_f32 v18, 0, v53
	ds_write_b16_d16_hi v17, v18 offset:4720
	v_cvt_pk_bf16_f32 v18, 0, v54
	ds_write_b16_d16_hi v17, v18 offset:4992
	v_cvt_pk_bf16_f32 v18, 0, v55
	ds_write_b16_d16_hi v17, v18 offset:5264
	v_cvt_pk_bf16_f32 v18, 0, v44
	ds_write_b16_d16_hi v17, v18 offset:8704
	v_cvt_pk_bf16_f32 v18, 0, v45
	ds_write_b16_d16_hi v17, v18 offset:8976
	v_cvt_pk_bf16_f32 v18, 0, v46
	ds_write_b16_d16_hi v17, v18 offset:9248
	v_cvt_pk_bf16_f32 v18, 0, v47
	ds_write_b16_d16_hi v17, v18 offset:9520
	v_cvt_pk_bf16_f32 v18, 0, v40
	ds_write_b16_d16_hi v17, v18 offset:8736
	v_cvt_pk_bf16_f32 v18, 0, v41
	ds_write_b16_d16_hi v17, v18 offset:9008
	v_cvt_pk_bf16_f32 v18, 0, v42
	ds_write_b16_d16_hi v17, v18 offset:9280
	v_cvt_pk_bf16_f32 v18, 0, v43
	ds_write_b16_d16_hi v17, v18 offset:9552
	v_cvt_pk_bf16_f32 v18, 0, v36
	ds_write_b16_d16_hi v17, v18 offset:8768
	v_cvt_pk_bf16_f32 v18, 0, v37
	ds_write_b16_d16_hi v17, v18 offset:9040
	v_cvt_pk_bf16_f32 v18, 0, v38
	ds_write_b16_d16_hi v17, v18 offset:9312
	v_cvt_pk_bf16_f32 v18, 0, v39
	ds_write_b16_d16_hi v17, v18 offset:9584
	v_cvt_pk_bf16_f32 v18, 0, v28
	ds_write_b16_d16_hi v17, v18 offset:8800
	v_cvt_pk_bf16_f32 v18, 0, v29
	ds_write_b16_d16_hi v17, v18 offset:9072
	v_cvt_pk_bf16_f32 v18, 0, v30
	ds_write_b16_d16_hi v17, v18 offset:9344
	v_cvt_pk_bf16_f32 v18, 0, v31
	ds_write_b16_d16_hi v17, v18 offset:9616
	v_cvt_pk_bf16_f32 v0, 0, v0
	ds_write_b16_d16_hi v17, v0 offset:13056
	v_cvt_pk_bf16_f32 v0, 0, v1
	v_mfma_f32_16x16x32_bf16 v[4:7], v[48:51], v[104:107], v[88:91]
	ds_write_b16_d16_hi v17, v0 offset:13328
	v_cvt_pk_bf16_f32 v0, 0, v2
	ds_write_b16_d16_hi v17, v0 offset:13600
	v_cvt_pk_bf16_f32 v0, 0, v3
	ds_write_b16_d16_hi v17, v0 offset:13872
	s_nop 0
	s_nop 1
	v_cvt_pk_bf16_f32 v0, 0, v4
	ds_write_b16_d16_hi v17, v0 offset:13088
	v_cvt_pk_bf16_f32 v0, 0, v5
	v_mfma_f32_16x16x32_bf16 v[8:11], v[48:51], v[112:115], v[80:83]
	ds_write_b16_d16_hi v17, v0 offset:13360
	v_cvt_pk_bf16_f32 v0, 0, v6
	ds_write_b16_d16_hi v17, v0 offset:13632
	v_cvt_pk_bf16_f32 v0, 0, v7
	ds_write_b16_d16_hi v17, v0 offset:13904
	s_nop 0
	s_nop 1
	v_cvt_pk_bf16_f32 v0, 0, v8
	ds_write_b16_d16_hi v17, v0 offset:13120
	v_cvt_pk_bf16_f32 v0, 0, v9
	v_mfma_f32_16x16x32_bf16 v[12:15], v[48:51], v[108:111], v[56:59]
	ds_write_b16_d16_hi v17, v0 offset:13392
	v_cvt_pk_bf16_f32 v0, 0, v10
	ds_write_b16_d16_hi v17, v0 offset:13664
	v_cvt_pk_bf16_f32 v0, 0, v11
	ds_write_b16_d16_hi v17, v0 offset:13936
	s_nop 0
	s_nop 1
	v_cvt_pk_bf16_f32 v0, 0, v12
	ds_write_b16_d16_hi v17, v0 offset:13152
	v_cvt_pk_bf16_f32 v0, 0, v13
	ds_write_b16_d16_hi v17, v0 offset:13424
	v_cvt_pk_bf16_f32 v0, 0, v14
	ds_write_b16_d16_hi v17, v0 offset:13696
	s_lshl_b64 s[14:15], s[14:15], 1
	v_cvt_pk_bf16_f32 v0, 0, v15
	s_add_u32 s14, s26, s14
	ds_write_b16_d16_hi v17, v0 offset:13968
	v_ashrrev_i32_e32 v0, 31, v16
	s_addc_u32 s15, s27, s15
	s_lshl_b32 s12, s12, 7
	v_lshrrev_b32_e32 v0, 28, v0
	s_ashr_i32 s13, s12, 31
	v_add_u32_e32 v0, v16, v0
	s_lshl_b64 s[12:13], s[12:13], 1
	v_ashrrev_i32_e32 v4, 4, v0
	v_and_b32_e32 v0, -16, v0
	s_add_u32 s12, s14, s12
	v_sub_u32_e32 v0, v16, v0
	v_ashrrev_i32_e32 v5, 31, v4
	s_addc_u32 s13, s15, s13
	v_mul_lo_u32 v1, v4, s42
	v_lshlrev_b32_e32 v6, 3, v0
	v_lshlrev_b64 v[4:5], 11, v[4:5]
	v_ashrrev_i32_e32 v7, 31, v6
	v_lshl_add_u64 v[4:5], s[12:13], 0, v[4:5]
	v_lshl_add_u64 v[8:9], v[6:7], 1, v[4:5]
	v_add_u32_e32 v4, 0x100, v16
	v_ashrrev_i32_e32 v5, 31, v4
	v_cvt_pk_bf16_f32 v19, 0, v100
	v_lshl_add_u32 v0, v0, 4, v1
	v_lshrrev_b32_e32 v5, 28, v5
	ds_write_b16_d16_hi v17, v19
	s_waitcnt lgkmcnt(0)
	s_barrier
; template <int WM, int WN>
; __device__ __forceinline__ void store_tile_bf16(const f32x4 (&acc)[WM][WN], u16* dst, int ld, char* smem) {
;     ...
;   constexpr int CPR = BN / 8;
; #pragma unroll
;   for (int i = 0; i < BM * CPR / 256; ++i) {
;     int q = tid + 256 * i, row = q / CPR, c = q % CPR;
;     uint4 v = *reinterpret_cast<const uint4*>(T + row * STR + c * 8);
;     *reinterpret_cast<uint4*>(dst + (size_t)row * ld + c * 8) = v;
;   }
	ds_read_b128 v[0:3], v0
	v_add_u32_e32 v5, v4, v5
	v_ashrrev_i32_e32 v10, 4, v5
	v_and_b32_e32 v5, -16, v5
	v_sub_u32_e32 v11, v4, v5
	v_mul_lo_u32 v4, v10, s42
	v_lshl_add_u32 v4, v11, 4, v4
	ds_read_b128 v[4:7], v4
	s_waitcnt lgkmcnt(1)
	global_store_dwordx4 v[8:9], v[0:3], off
	s_add_i32 s43, s43, s61
	s_cmp_lt_i32 s43, s62
	v_lshlrev_b32_e32 v0, 3, v11
	v_ashrrev_i32_e32 v11, 31, v10
	v_lshlrev_b64 v[2:3], 11, v[10:11]
	v_ashrrev_i32_e32 v1, 31, v0
	v_lshl_add_u64 v[2:3], s[12:13], 0, v[2:3]
	v_lshl_add_u64 v[0:1], v[0:1], 1, v[2:3]
	s_waitcnt lgkmcnt(0)
	global_store_dwordx4 v[0:1], v[4:7], off
	v_add_u32_e32 v0, 0x200, v16
	v_ashrrev_i32_e32 v1, 31, v0
	v_lshrrev_b32_e32 v1, 28, v1
	v_add_u32_e32 v1, v0, v1
	v_ashrrev_i32_e32 v4, 4, v1
	v_and_b32_e32 v1, -16, v1
	v_sub_u32_e32 v0, v0, v1
	v_ashrrev_i32_e32 v5, 31, v4
	v_mul_lo_u32 v1, v4, s42
	v_lshlrev_b32_e32 v6, 3, v0
	v_lshlrev_b64 v[4:5], 11, v[4:5]
	v_ashrrev_i32_e32 v7, 31, v6
	v_lshl_add_u64 v[4:5], s[12:13], 0, v[4:5]
	v_lshl_add_u64 v[8:9], v[6:7], 1, v[4:5]
	v_add_u32_e32 v4, 0x300, v16
	v_ashrrev_i32_e32 v5, 31, v4
	v_lshl_add_u32 v0, v0, 4, v1
	v_lshrrev_b32_e32 v5, 28, v5
	ds_read_b128 v[0:3], v0
	v_add_u32_e32 v5, v4, v5
	v_ashrrev_i32_e32 v10, 4, v5
	v_and_b32_e32 v5, -16, v5
	v_sub_u32_e32 v11, v4, v5
	v_mul_lo_u32 v4, v10, s42
	v_lshl_add_u32 v4, v11, 4, v4
	ds_read_b128 v[4:7], v4
	s_waitcnt lgkmcnt(1)
	global_store_dwordx4 v[8:9], v[0:3], off
	s_nop 1
	v_lshlrev_b32_e32 v0, 3, v11
	v_ashrrev_i32_e32 v11, 31, v10
	v_lshlrev_b64 v[2:3], 11, v[10:11]
	v_ashrrev_i32_e32 v1, 31, v0
	v_lshl_add_u64 v[2:3], s[12:13], 0, v[2:3]
	v_lshl_add_u64 v[0:1], v[0:1], 1, v[2:3]
	s_waitcnt lgkmcnt(0)
	global_store_dwordx4 v[0:1], v[4:7], off
	v_add_u32_e32 v0, 0x400, v16
	v_ashrrev_i32_e32 v1, 31, v0
	v_lshrrev_b32_e32 v1, 28, v1
	v_add_u32_e32 v1, v0, v1
	v_ashrrev_i32_e32 v4, 4, v1
	v_and_b32_e32 v1, -16, v1
	v_sub_u32_e32 v0, v0, v1
	v_ashrrev_i32_e32 v5, 31, v4
	v_mul_lo_u32 v1, v4, s42
	v_lshlrev_b32_e32 v6, 3, v0
	v_lshlrev_b64 v[4:5], 11, v[4:5]
	v_ashrrev_i32_e32 v7, 31, v6
	v_lshl_add_u64 v[4:5], s[12:13], 0, v[4:5]
	v_lshl_add_u64 v[8:9], v[6:7], 1, v[4:5]
	v_add_u32_e32 v4, 0x500, v16
	v_ashrrev_i32_e32 v5, 31, v4
	v_lshl_add_u32 v0, v0, 4, v1
	v_lshrrev_b32_e32 v5, 28, v5
	ds_read_b128 v[0:3], v0
	v_add_u32_e32 v5, v4, v5
	v_ashrrev_i32_e32 v10, 4, v5
	v_and_b32_e32 v5, -16, v5
	v_sub_u32_e32 v11, v4, v5
	v_mul_lo_u32 v4, v10, s42
	v_lshl_add_u32 v4, v11, 4, v4
	ds_read_b128 v[4:7], v4
	s_waitcnt lgkmcnt(1)
	global_store_dwordx4 v[8:9], v[0:3], off
	s_nop 1
	v_lshlrev_b32_e32 v0, 3, v11
	v_ashrrev_i32_e32 v11, 31, v10
	v_lshlrev_b64 v[2:3], 11, v[10:11]
	v_ashrrev_i32_e32 v1, 31, v0
	v_lshl_add_u64 v[2:3], s[12:13], 0, v[2:3]
	v_lshl_add_u64 v[0:1], v[0:1], 1, v[2:3]
	s_waitcnt lgkmcnt(0)
	global_store_dwordx4 v[0:1], v[4:7], off
	v_add_u32_e32 v0, 0x600, v16
	v_ashrrev_i32_e32 v1, 31, v0
	v_lshrrev_b32_e32 v1, 28, v1
	v_add_u32_e32 v1, v0, v1
	v_ashrrev_i32_e32 v4, 4, v1
	v_and_b32_e32 v1, -16, v1
	v_sub_u32_e32 v0, v0, v1
	v_ashrrev_i32_e32 v5, 31, v4
	v_mul_lo_u32 v1, v4, s42
	v_lshlrev_b32_e32 v6, 3, v0
	v_lshlrev_b64 v[4:5], 11, v[4:5]
	v_ashrrev_i32_e32 v7, 31, v6
	v_lshl_add_u64 v[4:5], s[12:13], 0, v[4:5]
	v_lshl_add_u64 v[8:9], v[6:7], 1, v[4:5]
	v_add_u32_e32 v4, 0x700, v16
	v_ashrrev_i32_e32 v5, 31, v4
	v_lshl_add_u32 v0, v0, 4, v1
	v_lshrrev_b32_e32 v5, 28, v5
	ds_read_b128 v[0:3], v0
	v_add_u32_e32 v5, v4, v5
	v_ashrrev_i32_e32 v10, 4, v5
	v_and_b32_e32 v5, -16, v5
	v_sub_u32_e32 v11, v4, v5
	v_mul_lo_u32 v4, v10, s42
	v_lshl_add_u32 v4, v11, 4, v4
	ds_read_b128 v[4:7], v4
	s_waitcnt lgkmcnt(1)
	global_store_dwordx4 v[8:9], v[0:3], off
	s_nop 1
	v_lshlrev_b32_e32 v0, 3, v11
	v_ashrrev_i32_e32 v11, 31, v10
	v_lshlrev_b64 v[2:3], 11, v[10:11]
	v_ashrrev_i32_e32 v1, 31, v0
	v_lshl_add_u64 v[2:3], s[12:13], 0, v[2:3]
	v_lshl_add_u64 v[0:1], v[0:1], 1, v[2:3]
	s_waitcnt lgkmcnt(0)
	global_store_dwordx4 v[0:1], v[4:7], off
	s_cbranch_scc1 .LBB0_638

; __device__ __forceinline__ float bflo(unsigned w) { return __uint_as_float(w << 16); }
; __device__ __forceinline__ float bfhi(unsigned w) { return __uint_as_float(w & 0xffff0000u); }
; __device__ void norm_phase(const Params& p, int layer) {
;     ...
;       const float* xr = (layer == 0) ? p.x : p.out;
;       float4 ov[8];
;       float ss = 0.f;
; #pragma unroll
;       for (int i = 0; i < 8; ++i) {
;         {
;           uint2 ob = *reinterpret_cast<const uint2*>(OUTB + rbase + i * 128);
;           ov[i] = make_float4(bflo(ob.x), bfhi(ob.x), bflo(ob.y), bfhi(ob.y));
;         }
;         xv[i] = *reinterpret_cast<const float4*>(xr + rbase + i * 128);
;       }
; #pragma unroll
;       for (int i = 0; i < 8; ++i) ss += ov[i].x * ov[i].x + ov[i].y * ov[i].y + ov[i].z * ov[i].z + ov[i].w * ov[i].w;
;       ss = half_wave_sum(ss);
;       float rstd = rsqrtf(ss * (1.f / 1024.f) + 1e-6f);
; #pragma unroll
;       for (int i = 0; i < 8; ++i) {
;         float4 g = *reinterpret_cast<const float4*>(p.g_post + (size_t)layer * DM + l32 * 4 + i * 128);
;         xv[i].x += ov[i].x * rstd * g.x;
;         xv[i].y += ov[i].y * rstd * g.y;
;         xv[i].z += ov[i].z * rstd * g.z;
;         xv[i].w += ov[i].w * rstd * g.w;
;         *reinterpret_cast<float4*>(p.out + rbase + i * 128) = xv[i];
;       }
.LBB0_680:
	v_ashrrev_i32_e32 v39, 31, v38
	v_lshlrev_b64 v[4:5], 10, v[38:39]
	v_or_b32_e32 v4, v4, v32
	v_lshlrev_b64 v[40:41], 1, v[4:5]
	v_lshl_add_u64 v[6:7], s[16:17], 0, v[40:41]
	global_load_dwordx2 v[12:13], v[6:7], off
	global_load_dwordx2 v[14:15], v[6:7], off offset:256
	global_load_dwordx2 v[16:17], v[6:7], off offset:512
	global_load_dwordx2 v[18:19], v[6:7], off offset:768
	global_load_dwordx2 v[20:21], v[6:7], off offset:1024
	global_load_dwordx2 v[22:23], v[6:7], off offset:1280
	global_load_dwordx2 v[24:25], v[6:7], off offset:1536
	global_load_dwordx2 v[26:27], v[6:7], off offset:1792
	global_load_dwordx4 v[0:3], v[34:35], off
	v_lshl_add_u64 v[42:43], v[4:5], 2, s[20:21]
	global_load_dwordx4 v[8:11], v[42:43], off
	v_lshl_add_u64 v[40:41], s[14:15], 0, v[40:41]
	v_add_u32_e32 v33, s56, v33
	v_add_u32_e32 v38, s24, v38
	s_waitcnt vmcnt(9)
	v_lshlrev_b32_e32 v28, 16, v12
	v_and_b32_e32 v29, 0xffff0000, v12
	s_waitcnt vmcnt(8)
	v_lshlrev_b32_e32 v52, 16, v14
	v_and_b32_e32 v53, 0xffff0000, v14
	s_waitcnt vmcnt(7)
	v_and_b32_e32 v57, 0xffff0000, v16
	s_waitcnt vmcnt(6)
	v_and_b32_e32 v59, 0xffff0000, v18
	v_lshlrev_b32_e32 v30, 16, v13
	v_and_b32_e32 v31, 0xffff0000, v13
	v_lshlrev_b32_e32 v54, 16, v15
	v_and_b32_e32 v55, 0xffff0000, v15
	v_lshlrev_b32_e32 v56, 16, v16
	v_lshlrev_b32_e32 v58, 16, v18
	s_waitcnt vmcnt(5)
	v_lshlrev_b32_e32 v60, 16, v20
	v_and_b32_e32 v61, 0xffff0000, v20
	v_lshlrev_b32_e32 v62, 16, v21
	v_and_b32_e32 v63, 0xffff0000, v21
	s_waitcnt vmcnt(2)
	v_lshlrev_b32_e32 v6, 16, v26
	v_and_b32_e32 v7, 0xffff0000, v26
	v_lshlrev_b32_e32 v4, 16, v27
	v_and_b32_e32 v5, 0xffff0000, v27
	v_pk_mul_f32 v[12:13], v[28:29], v[28:29]
	v_pk_mul_f32 v[20:21], v[52:53], v[52:53]
	v_mov_b32_e32 v26, v57
	v_mov_b32_e32 v27, v59
	v_lshlrev_b32_e32 v16, 16, v17
	v_lshlrev_b32_e32 v18, 16, v19
	v_lshlrev_b32_e32 v64, 16, v22
	v_and_b32_e32 v65, 0xffff0000, v22
	v_lshlrev_b32_e32 v66, 16, v23
	v_and_b32_e32 v67, 0xffff0000, v23
	v_lshlrev_b32_e32 v68, 16, v24
	v_and_b32_e32 v69, 0xffff0000, v24
	v_lshlrev_b32_e32 v70, 16, v25
	v_and_b32_e32 v71, 0xffff0000, v25
	v_pk_mul_f32 v[14:15], v[30:31], v[30:31]
	v_pk_mul_f32 v[22:23], v[54:55], v[54:55]
	v_mov_b32_e32 v24, v56
	v_mov_b32_e32 v25, v58
	v_pk_mul_f32 v[26:27], v[26:27], v[26:27]
	v_add_f32_e32 v39, v20, v21
	v_add_f32_e32 v12, v12, v13
	v_and_b32_e32 v17, 0xffff0000, v17
	v_and_b32_e32 v19, 0xffff0000, v19
	v_mov_b32_e32 v72, v16
	v_mov_b32_e32 v73, v18
	v_mov_b32_e32 v78, v61
	v_mov_b32_e32 v79, v65
	v_pk_fma_f32 v[20:21], v[24:25], v[24:25], v[26:27]
	v_add_f32_e32 v22, v39, v22
	v_add_f32_e32 v12, v12, v14
	v_mov_b32_e32 v74, v17
	v_mov_b32_e32 v75, v19
	v_mov_b32_e32 v76, v60
	v_mov_b32_e32 v77, v64
	v_pk_mul_f32 v[78:79], v[78:79], v[78:79]
	v_pk_fma_f32 v[20:21], v[72:73], v[72:73], v[20:21]
	v_add_f32_e32 v39, v23, v22
	v_add_f32_e32 v12, v15, v12
	v_mov_b32_e32 v80, v62
	v_mov_b32_e32 v81, v66
	v_mov_b32_e32 v86, v69
	v_mov_b32_e32 v87, v7
	v_pk_fma_f32 v[24:25], v[76:77], v[76:77], v[78:79]
	v_pk_fma_f32 v[20:21], v[74:75], v[74:75], v[20:21]
	v_add_f32_e32 v12, v12, v39
	v_mov_b32_e32 v82, v63
	v_mov_b32_e32 v83, v67
	v_mov_b32_e32 v84, v68
	v_mov_b32_e32 v85, v6
	v_pk_mul_f32 v[86:87], v[86:87], v[86:87]
	v_pk_fma_f32 v[24:25], v[80:81], v[80:81], v[24:25]
	v_add_f32_e32 v12, v12, v20
	v_mov_b32_e32 v88, v70
	v_mov_b32_e32 v89, v4
	v_pk_fma_f32 v[26:27], v[84:85], v[84:85], v[86:87]
	v_pk_fma_f32 v[22:23], v[82:83], v[82:83], v[24:25]
	v_add_f32_e32 v12, v12, v21
	v_mov_b32_e32 v90, v71
	v_mov_b32_e32 v91, v5
	v_pk_fma_f32 v[26:27], v[88:89], v[88:89], v[26:27]
	v_add_f32_e32 v12, v12, v22
	v_pk_fma_f32 v[24:25], v[90:91], v[90:91], v[26:27]
	v_add_f32_e32 v12, v12, v23
	v_add_f32_e32 v12, v12, v24
	v_add_f32_e32 v12, v12, v25
	ds_bpermute_b32 v13, v44, v12
	s_waitcnt lgkmcnt(0)
	v_add_f32_e32 v12, v12, v13
	ds_bpermute_b32 v13, v45, v12
	s_waitcnt lgkmcnt(0)
	v_add_f32_e32 v12, v12, v13
	ds_bpermute_b32 v13, v46, v12
	s_waitcnt lgkmcnt(0)
	v_add_f32_e32 v12, v12, v13
	ds_bpermute_b32 v13, v47, v12
	s_waitcnt lgkmcnt(0)
	v_add_f32_e32 v12, v12, v13
	ds_bpermute_b32 v13, v48, v12
	s_waitcnt lgkmcnt(0)
	v_add_f32_e32 v12, v12, v13
	v_fmamk_f32 v12, v12, 0x3a800000, v49
	v_mul_f32_e32 v13, 0x4b800000, v12
	v_cmp_gt_f32_e32 vcc, s25, v12
	s_nop 1
	v_cndmask_b32_e32 v12, v12, v13, vcc
	v_rsq_f32_e32 v20, v12
	global_load_dwordx4 v[12:15], v[42:43], off offset:512
	v_mul_f32_e32 v21, 0x45800000, v20
	v_cndmask_b32_e32 v72, v20, v21, vcc
	v_pk_mul_f32 v[20:21], v[72:73], v[28:29] op_sel_hi:[0,1]
	v_pk_mul_f32 v[22:23], v[72:73], v[30:31] op_sel_hi:[0,1]
	s_waitcnt vmcnt(1)
	v_pk_fma_f32 v[28:29], v[0:1], v[20:21], v[8:9]
	v_pk_fma_f32 v[30:31], v[2:3], v[22:23], v[10:11]
	global_store_dwordx4 v[42:43], v[28:31], off
	global_load_dwordx4 v[0:3], v[34:35], off offset:512
	v_pk_mul_f32 v[8:9], v[72:73], v[52:53] op_sel_hi:[0,1]
	v_pk_mul_f32 v[10:11], v[72:73], v[54:55] op_sel_hi:[0,1]
	v_pk_mul_f32 v[20:21], v[72:73], v[56:57] op_sel_hi:[0,1]
	v_pk_mul_f32 v[16:17], v[72:73], v[16:17] op_sel_hi:[0,1]
	v_pk_mul_f32 v[6:7], v[72:73], v[6:7] op_sel_hi:[0,1]
	s_waitcnt vmcnt(0)
	v_pk_fma_f32 v[24:25], v[8:9], v[0:1], v[12:13]
	v_pk_fma_f32 v[26:27], v[10:11], v[2:3], v[14:15]
	global_store_dwordx4 v[42:43], v[24:27], off offset:512
	global_load_dwordx4 v[0:3], v[34:35], off offset:1024
	global_load_dwordx4 v[8:11], v[42:43], off offset:1024
	global_load_dwordx4 v[12:15], v[42:43], off offset:1536
	s_waitcnt vmcnt(1)
; __device__ __forceinline__ unsigned pack2(float a, float b) { return (unsigned)f2bf(a) | ((unsigned)f2bf(b) << 16); }
; __device__ void norm_phase(const Params& p, int layer) {
;     ...
;       for (int i = 0; i < 8; ++i) {
;         float4 g = *reinterpret_cast<const float4*>(p.g_post + (size_t)layer * DM + l32 * 4 + i * 128);
;         xv[i].x += ov[i].x * rstd * g.x;
;         xv[i].y += ov[i].y * rstd * g.y;
;         xv[i].z += ov[i].z * rstd * g.z;
;         xv[i].w += ov[i].w * rstd * g.w;
;         *reinterpret_cast<float4*>(p.out + rbase + i * 128) = xv[i];
;       }
;     }
;     const int nl = layer + 1;
;     if (nl < 4) {
;       float ss = 0.f;
; #pragma unroll
;       for (int i = 0; i < 8; ++i) ss += xv[i].x * xv[i].x + xv[i].y * xv[i].y + xv[i].z * xv[i].z + xv[i].w * xv[i].w;
;       ss = half_wave_sum(ss);
;       float rstd = rsqrtf(ss * (1.f / 1024.f) + 1e-6f);
; #pragma unroll
;       for (int i = 0; i < 8; ++i) {
;         float4 g = *reinterpret_cast<const float4*>(p.g_pre + (size_t)nl * DM + l32 * 4 + i * 128);
;         uint2 o;
;         o.x = pack2(xv[i].x * rstd * g.x, xv[i].y * rstd * g.y);
;         o.y = pack2(xv[i].z * rstd * g.z, xv[i].w * rstd * g.w);
;         *reinterpret_cast<uint2*>(H + rbase + i * 128) = o;
	v_pk_fma_f32 v[20:21], v[20:21], v[0:1], v[8:9]
	v_pk_fma_f32 v[22:23], v[16:17], v[2:3], v[10:11]
	global_store_dwordx4 v[42:43], v[20:23], off offset:1024
	global_load_dwordx4 v[0:3], v[34:35], off offset:1536
	v_pk_mul_f32 v[8:9], v[72:73], v[58:59] op_sel_hi:[0,1]
	v_pk_mul_f32 v[10:11], v[72:73], v[18:19] op_sel_hi:[0,1]
	s_waitcnt vmcnt(0)
	v_pk_fma_f32 v[16:17], v[8:9], v[0:1], v[12:13]
	v_pk_fma_f32 v[18:19], v[10:11], v[2:3], v[14:15]
	global_store_dwordx4 v[42:43], v[16:19], off offset:1536
	global_load_dwordx4 v[0:3], v[34:35], off offset:2048
	global_load_dwordx4 v[8:11], v[42:43], off offset:2048
	global_load_dwordx4 v[52:55], v[42:43], off offset:2560
	v_pk_mul_f32 v[12:13], v[72:73], v[60:61] op_sel_hi:[0,1]
	v_pk_mul_f32 v[14:15], v[72:73], v[62:63] op_sel_hi:[0,1]
	v_pk_mul_f32 v[60:61], v[72:73], v[68:69] op_sel_hi:[0,1]
	v_pk_mul_f32 v[62:63], v[72:73], v[70:71] op_sel_hi:[0,1]
	v_mov_b32_e32 v68, v23
	v_mov_b32_e32 v69, v19
	s_waitcnt vmcnt(1)
	v_pk_fma_f32 v[12:13], v[12:13], v[0:1], v[8:9]
	v_pk_fma_f32 v[14:15], v[14:15], v[2:3], v[10:11]
	global_store_dwordx4 v[42:43], v[12:15], off offset:2048
	global_load_dwordx4 v[0:3], v[34:35], off offset:2560
	v_pk_mul_f32 v[8:9], v[72:73], v[64:65] op_sel_hi:[0,1]
	v_pk_mul_f32 v[10:11], v[72:73], v[66:67] op_sel_hi:[0,1]
	v_mov_b32_e32 v64, v21
	v_mov_b32_e32 v65, v17
	v_mov_b32_e32 v66, v22
	v_mov_b32_e32 v67, v18
	s_waitcnt vmcnt(0)
	v_pk_fma_f32 v[8:9], v[8:9], v[0:1], v[52:53]
	v_pk_fma_f32 v[10:11], v[10:11], v[2:3], v[54:55]
	global_store_dwordx4 v[42:43], v[8:11], off offset:2560
	global_load_dwordx4 v[0:3], v[34:35], off offset:3072
	global_load_dwordx4 v[52:55], v[42:43], off offset:3072
	global_load_dwordx4 v[56:59], v[42:43], off offset:3584
	s_waitcnt vmcnt(1)
	v_pk_fma_f32 v[0:1], v[60:61], v[0:1], v[52:53]
	v_pk_fma_f32 v[2:3], v[62:63], v[2:3], v[54:55]
	global_store_dwordx4 v[42:43], v[0:3], off offset:3072
	global_load_dwordx4 v[52:55], v[34:35], off offset:3584
	v_pk_mul_f32 v[60:61], v[72:73], v[4:5] op_sel_hi:[0,1]
	v_pk_mul_f32 v[4:5], v[28:29], v[28:29]
	v_pk_mul_f32 v[62:63], v[30:31], v[30:31]
	v_add_f32_e32 v4, v4, v5
	v_add_f32_e32 v4, v62, v4
	v_add_f32_e32 v39, v63, v4
	v_pk_mul_f32 v[4:5], v[24:25], v[24:25]
	v_pk_mul_f32 v[62:63], v[26:27], v[26:27]
	v_add_f32_e32 v4, v4, v5
	v_add_f32_e32 v4, v4, v62
	v_add_f32_e32 v4, v4, v63
	v_add_f32_e32 v39, v39, v4
	v_mov_b32_e32 v62, v20
	v_mov_b32_e32 v63, v16
	s_waitcnt vmcnt(0)
	v_pk_fma_f32 v[4:5], v[6:7], v[52:53], v[56:57]
	v_pk_fma_f32 v[6:7], v[60:61], v[54:55], v[58:59]
	global_store_dwordx4 v[42:43], v[4:7], off offset:3584
	global_load_dwordx4 v[52:55], v[36:37], off
	v_pk_mul_f32 v[42:43], v[64:65], v[64:65]
	v_mov_b32_e32 v56, v13
	v_pk_fma_f32 v[42:43], v[62:63], v[62:63], v[42:43]
	v_mov_b32_e32 v57, v9
	v_pk_fma_f32 v[42:43], v[66:67], v[66:67], v[42:43]
	v_pk_mul_f32 v[56:57], v[56:57], v[56:57]
	v_pk_fma_f32 v[42:43], v[68:69], v[68:69], v[42:43]
	v_mov_b32_e32 v58, v14
	v_add_f32_e32 v39, v39, v42
	v_add_f32_e32 v39, v39, v43
	v_mov_b32_e32 v42, v12
	v_mov_b32_e32 v43, v8
	v_mov_b32_e32 v59, v10
	v_pk_fma_f32 v[42:43], v[42:43], v[42:43], v[56:57]
	v_mov_b32_e32 v60, v15
	v_mov_b32_e32 v61, v11
	v_pk_fma_f32 v[42:43], v[58:59], v[58:59], v[42:43]
	v_mov_b32_e32 v56, v1
	v_pk_fma_f32 v[42:43], v[60:61], v[60:61], v[42:43]
	v_mov_b32_e32 v57, v5
	v_add_f32_e32 v39, v39, v42
	v_add_f32_e32 v39, v39, v43
	v_mov_b32_e32 v42, v0
	v_mov_b32_e32 v43, v4
	v_pk_mul_f32 v[56:57], v[56:57], v[56:57]
	v_mov_b32_e32 v58, v2
	v_mov_b32_e32 v59, v6
	v_pk_fma_f32 v[42:43], v[42:43], v[42:43], v[56:57]
	v_mov_b32_e32 v60, v3
	v_mov_b32_e32 v61, v7
	v_pk_fma_f32 v[42:43], v[58:59], v[58:59], v[42:43]
	s_waitcnt vmcnt(0)
	v_mov_b32_e32 v57, v54
	v_pk_fma_f32 v[42:43], v[60:61], v[60:61], v[42:43]
	v_mov_b32_e32 v54, v53
	v_add_f32_e32 v39, v39, v42
	v_add_f32_e32 v39, v39, v43
	ds_bpermute_b32 v42, v44, v39
	v_mov_b32_e32 v43, v30
	v_mov_b32_e32 v30, v29
	v_mov_b32_e32 v56, v52
	s_waitcnt lgkmcnt(0)
	v_add_f32_e32 v39, v39, v42
	ds_bpermute_b32 v42, v45, v39
	s_waitcnt lgkmcnt(0)
	v_add_f32_e32 v39, v39, v42
	ds_bpermute_b32 v42, v46, v39
	s_waitcnt lgkmcnt(0)
	v_add_f32_e32 v39, v39, v42
	ds_bpermute_b32 v42, v47, v39
	s_waitcnt lgkmcnt(0)
	v_add_f32_e32 v39, v39, v42
	ds_bpermute_b32 v42, v48, v39
	s_waitcnt lgkmcnt(0)
	v_add_f32_e32 v39, v39, v42
	v_fmamk_f32 v39, v39, 0x3a800000, v49
	v_mul_f32_e32 v42, 0x4b800000, v39
	v_cmp_gt_f32_e32 vcc, s25, v39
	s_nop 1
	v_cndmask_b32_e32 v39, v39, v42, vcc
	v_rsq_f32_e32 v39, v39
	v_mov_b32_e32 v42, v28
	v_mul_f32_e32 v28, 0x45800000, v39
	v_cndmask_b32_e32 v28, v39, v28, vcc
	v_pk_mul_f32 v[30:31], v[30:31], v[28:29] op_sel_hi:[1,0]
	v_pk_mul_f32 v[42:43], v[42:43], v[28:29] op_sel_hi:[1,0]
	v_pk_mul_f32 v[30:31], v[54:55], v[30:31]
	v_pk_mul_f32 v[42:43], v[56:57], v[42:43]
	v_cvt_pk_bf16_f32 v31, 0, v31
	v_cvt_pk_bf16_f32 v30, 0, v30
	v_cvt_pk_bf16_f32 v39, 0, v42
	v_cvt_pk_bf16_f32 v29, 0, v43
	v_and_b32_e32 v31, 0xffff0000, v31
	v_and_b32_e32 v30, 0xffff0000, v30
	v_or_b32_sdwa v31, v31, v29 dst_sel:DWORD dst_unused:UNUSED_PAD src0_sel:DWORD src1_sel:WORD_1
	v_or_b32_sdwa v30, v30, v39 dst_sel:DWORD dst_unused:UNUSED_PAD src0_sel:DWORD src1_sel:WORD_1
	global_store_dwordx2 v[40:41], v[30:31], off
	global_load_dwordx4 v[52:55], v[36:37], off offset:512
	v_mov_b32_e32 v30, v24
	v_mov_b32_e32 v31, v26
	v_mov_b32_e32 v26, v25
	v_pk_mul_f32 v[24:25], v[30:31], v[28:29] op_sel_hi:[1,0]
	v_pk_mul_f32 v[26:27], v[26:27], v[28:29] op_sel_hi:[1,0]
	v_cmp_lt_i32_e32 vcc, s27, v33
	s_or_b64 s[22:23], vcc, s[22:23]
	s_waitcnt vmcnt(0)
; __device__ __forceinline__ unsigned pack2(float a, float b) { return (unsigned)f2bf(a) | ((unsigned)f2bf(b) << 16); }
; __device__ void norm_phase(const Params& p, int layer) {
;     ...
; #pragma unroll
;       for (int i = 0; i < 8; ++i) {
;         float4 g = *reinterpret_cast<const float4*>(p.g_pre + (size_t)nl * DM + l32 * 4 + i * 128);
;         uint2 o;
;         o.x = pack2(xv[i].x * rstd * g.x, xv[i].y * rstd * g.y);
;         o.y = pack2(xv[i].z * rstd * g.z, xv[i].w * rstd * g.w);
;         *reinterpret_cast<uint2*>(H + rbase + i * 128) = o;
;       }
	v_mov_b32_e32 v31, v54
	v_mov_b32_e32 v54, v53
	v_mov_b32_e32 v30, v52
	v_pk_mul_f32 v[26:27], v[54:55], v[26:27]
	v_pk_mul_f32 v[24:25], v[30:31], v[24:25]
	v_and_b32_sdwa v29, v25, v50 dst_sel:DWORD dst_unused:UNUSED_PAD src0_sel:WORD_1 src1_sel:DWORD
	v_cvt_pk_bf16_f32 v27, 0, v27
	v_cvt_pk_bf16_f32 v26, 0, v26
	v_cvt_pk_bf16_f32 v24, 0, v24
	v_cvt_pk_bf16_f32 v25, 0, v25
	v_and_b32_e32 v27, 0xffff0000, v27
	v_and_b32_e32 v26, 0xffff0000, v26
	v_or_b32_sdwa v25, v27, v25 dst_sel:DWORD dst_unused:UNUSED_PAD src0_sel:DWORD src1_sel:WORD_1
	v_or_b32_sdwa v24, v26, v24 dst_sel:DWORD dst_unused:UNUSED_PAD src0_sel:DWORD src1_sel:WORD_1
	global_store_dwordx2 v[40:41], v[24:25], off offset:256
	global_load_dwordx4 v[24:27], v[36:37], off offset:1024
	v_mov_b32_e32 v30, v20
	v_mov_b32_e32 v31, v22
	v_mov_b32_e32 v22, v21
	v_pk_mul_f32 v[20:21], v[30:31], v[28:29] op_sel_hi:[1,0]
	v_pk_mul_f32 v[22:23], v[22:23], v[28:29] op_sel_hi:[1,0]
	s_waitcnt vmcnt(0)
	v_mov_b32_e32 v31, v26
	v_mov_b32_e32 v26, v25
	v_mov_b32_e32 v30, v24
	v_pk_mul_f32 v[22:23], v[22:23], v[26:27]
	v_pk_mul_f32 v[20:21], v[20:21], v[30:31]
	v_cvt_pk_bf16_f32 v23, 0, v23
	v_cvt_pk_bf16_f32 v22, 0, v22
	v_cvt_pk_bf16_f32 v20, 0, v20
	v_cvt_pk_bf16_f32 v21, 0, v21
	v_and_b32_e32 v23, 0xffff0000, v23
	v_and_b32_e32 v22, 0xffff0000, v22
	v_or_b32_sdwa v21, v23, v21 dst_sel:DWORD dst_unused:UNUSED_PAD src0_sel:DWORD src1_sel:WORD_1
	v_or_b32_sdwa v20, v22, v20 dst_sel:DWORD dst_unused:UNUSED_PAD src0_sel:DWORD src1_sel:WORD_1
	global_store_dwordx2 v[40:41], v[20:21], off offset:512
	global_load_dwordx4 v[20:23], v[36:37], off offset:1536
	v_mov_b32_e32 v24, v16
	v_mov_b32_e32 v25, v18
	v_mov_b32_e32 v18, v17
	v_pk_mul_f32 v[16:17], v[24:25], v[28:29] op_sel_hi:[1,0]
	v_pk_mul_f32 v[18:19], v[18:19], v[28:29] op_sel_hi:[1,0]
	s_waitcnt vmcnt(0)
	v_mov_b32_e32 v25, v22
	v_mov_b32_e32 v22, v21
	v_mov_b32_e32 v24, v20
	v_pk_mul_f32 v[18:19], v[18:19], v[22:23]
	v_pk_mul_f32 v[16:17], v[16:17], v[24:25]
	v_cvt_pk_bf16_f32 v19, 0, v19
	v_cvt_pk_bf16_f32 v18, 0, v18
	v_cvt_pk_bf16_f32 v16, 0, v16
	v_cvt_pk_bf16_f32 v17, 0, v17
	v_and_b32_e32 v19, 0xffff0000, v19
	v_and_b32_e32 v18, 0xffff0000, v18
	v_or_b32_sdwa v17, v19, v17 dst_sel:DWORD dst_unused:UNUSED_PAD src0_sel:DWORD src1_sel:WORD_1
	v_or_b32_sdwa v16, v18, v16 dst_sel:DWORD dst_unused:UNUSED_PAD src0_sel:DWORD src1_sel:WORD_1
	global_store_dwordx2 v[40:41], v[16:17], off offset:768
	global_load_dwordx4 v[16:19], v[36:37], off offset:2048
	v_mov_b32_e32 v20, v12
	v_mov_b32_e32 v21, v14
	v_mov_b32_e32 v14, v13
	v_pk_mul_f32 v[12:13], v[20:21], v[28:29] op_sel_hi:[1,0]
	v_pk_mul_f32 v[14:15], v[14:15], v[28:29] op_sel_hi:[1,0]
	s_waitcnt vmcnt(0)
	v_mov_b32_e32 v21, v18
	v_mov_b32_e32 v18, v17
	v_mov_b32_e32 v20, v16
	v_pk_mul_f32 v[14:15], v[14:15], v[18:19]
	v_pk_mul_f32 v[12:13], v[12:13], v[20:21]
	v_cvt_pk_bf16_f32 v15, 0, v15
	v_cvt_pk_bf16_f32 v14, 0, v14
	v_cvt_pk_bf16_f32 v12, 0, v12
	v_cvt_pk_bf16_f32 v13, 0, v13
	v_and_b32_e32 v15, 0xffff0000, v15
	v_and_b32_e32 v14, 0xffff0000, v14
	v_or_b32_sdwa v13, v15, v13 dst_sel:DWORD dst_unused:UNUSED_PAD src0_sel:DWORD src1_sel:WORD_1
	v_or_b32_sdwa v12, v14, v12 dst_sel:DWORD dst_unused:UNUSED_PAD src0_sel:DWORD src1_sel:WORD_1
	global_store_dwordx2 v[40:41], v[12:13], off offset:1024
	global_load_dwordx4 v[12:15], v[36:37], off offset:2560
	v_mov_b32_e32 v16, v8
	v_mov_b32_e32 v17, v10
	v_mov_b32_e32 v10, v9
	v_pk_mul_f32 v[8:9], v[16:17], v[28:29] op_sel_hi:[1,0]
	v_pk_mul_f32 v[10:11], v[10:11], v[28:29] op_sel_hi:[1,0]
	s_waitcnt vmcnt(0)
	v_mov_b32_e32 v17, v14
	v_mov_b32_e32 v14, v13
	v_mov_b32_e32 v16, v12
	v_pk_mul_f32 v[10:11], v[10:11], v[14:15]
	v_pk_mul_f32 v[8:9], v[8:9], v[16:17]
	v_and_b32_sdwa v14, v11, v50 dst_sel:DWORD dst_unused:UNUSED_PAD src0_sel:WORD_1 src1_sel:DWORD
	v_and_b32_sdwa v15, v10, v50 dst_sel:DWORD dst_unused:UNUSED_PAD src0_sel:WORD_1 src1_sel:DWORD
	v_cvt_pk_bf16_f32 v11, 0, v11
	v_cvt_pk_bf16_f32 v10, 0, v10
	v_cvt_pk_bf16_f32 v8, 0, v8
	v_cvt_pk_bf16_f32 v9, 0, v9
	v_and_b32_e32 v11, 0xffff0000, v11
	v_and_b32_e32 v10, 0xffff0000, v10
	v_or_b32_sdwa v9, v11, v9 dst_sel:DWORD dst_unused:UNUSED_PAD src0_sel:DWORD src1_sel:WORD_1
	v_or_b32_sdwa v8, v10, v8 dst_sel:DWORD dst_unused:UNUSED_PAD src0_sel:DWORD src1_sel:WORD_1
	global_store_dwordx2 v[40:41], v[8:9], off offset:1280
	global_load_dwordx4 v[8:11], v[36:37], off offset:3072
	v_mov_b32_e32 v12, v0
	v_mov_b32_e32 v13, v2
	v_mov_b32_e32 v2, v1
	v_pk_mul_f32 v[0:1], v[12:13], v[28:29] op_sel_hi:[1,0]
	v_pk_mul_f32 v[2:3], v[2:3], v[28:29] op_sel_hi:[1,0]
	s_waitcnt vmcnt(0)
	v_mov_b32_e32 v13, v10
	v_mov_b32_e32 v10, v9
	v_mov_b32_e32 v12, v8
	v_pk_mul_f32 v[2:3], v[2:3], v[10:11]
	v_pk_mul_f32 v[0:1], v[0:1], v[12:13]
	v_cvt_pk_bf16_f32 v3, 0, v3
	v_cvt_pk_bf16_f32 v2, 0, v2
	v_cvt_pk_bf16_f32 v0, 0, v0
	v_cvt_pk_bf16_f32 v1, 0, v1
	v_and_b32_e32 v3, 0xffff0000, v3
	v_and_b32_e32 v2, 0xffff0000, v2
	v_or_b32_sdwa v1, v3, v1 dst_sel:DWORD dst_unused:UNUSED_PAD src0_sel:DWORD src1_sel:WORD_1
	v_or_b32_sdwa v0, v2, v0 dst_sel:DWORD dst_unused:UNUSED_PAD src0_sel:DWORD src1_sel:WORD_1
	global_store_dwordx2 v[40:41], v[0:1], off offset:1536
	global_load_dwordx4 v[0:3], v[36:37], off offset:3584
	v_mov_b32_e32 v8, v4
	v_mov_b32_e32 v9, v6
	v_mov_b32_e32 v6, v5
	v_pk_mul_f32 v[4:5], v[8:9], v[28:29] op_sel_hi:[1,0]
	v_pk_mul_f32 v[6:7], v[6:7], v[28:29] op_sel_hi:[1,0]
	s_waitcnt vmcnt(0)
	v_mov_b32_e32 v9, v2
	v_mov_b32_e32 v2, v1
	v_mov_b32_e32 v8, v0
	v_pk_mul_f32 v[2:3], v[6:7], v[2:3]
	v_pk_mul_f32 v[0:1], v[4:5], v[8:9]
	v_cvt_pk_bf16_f32 v3, 0, v3
	v_cvt_pk_bf16_f32 v2, 0, v2
	v_cvt_pk_bf16_f32 v0, 0, v0
	v_cvt_pk_bf16_f32 v1, 0, v1
	v_and_b32_e32 v3, 0xffff0000, v3
	v_and_b32_e32 v2, 0xffff0000, v2
	v_or_b32_sdwa v1, v3, v1 dst_sel:DWORD dst_unused:UNUSED_PAD src0_sel:DWORD src1_sel:WORD_1
	v_or_b32_sdwa v0, v2, v0 dst_sel:DWORD dst_unused:UNUSED_PAD src0_sel:DWORD src1_sel:WORD_1
	global_store_dwordx2 v[40:41], v[0:1], off offset:1792
	s_andn2_b64 exec, exec, s[22:23]
	s_cbranch_execnz .LBB0_680
	s_or_b64 exec, exec, s[22:23]
	v_mov_b64_e32 v[10:11], s[28:29]

; template <int WM, int WN>
; __device__ __forceinline__ void store_tile_bf16(const f32x4 (&acc)[WM][WN], u16* dst, int ld, char* smem) {
;   constexpr int BM = 32 * WM, BN = 32 * WN, STR = BN + 8;
;   const int tid = opaque_tid(), lane = tid & 63, wid = tid >> 6;
;   const int wr = wid >> 1, wc = wid & 1, fr = lane & 15, fq = lane >> 4;
;   u16* T = reinterpret_cast<u16*>(smem);
; #pragma unroll
;   for (int m = 0; m < WM; ++m)
; #pragma unroll
;     for (int n = 0; n < WN; ++n)
; #pragma unroll
;       for (int j = 0; j < 4; ++j)
;         T[(wr * 16 * WM + m * 16 + fq * 4 + j) * STR + wc * 16 * WN + n * 16 + fr] = f2bf(acc[m][n][j]);
;   __syncthreads();
;   constexpr int CPR = BN / 8;
; #pragma unroll
;   for (int i = 0; i < BM * CPR / 256; ++i) {
;     int q = tid + 256 * i, row = q / CPR, c = q % CPR;
;     uint4 v = *reinterpret_cast<const uint4*>(T + row * STR + c * 8);
;     *reinterpret_cast<uint4*>(dst + (size_t)row * ld + c * 8) = v;
; __device__ void phase_inproj(const Params& p, int layer, char* smem) {
;     ...
;     store_tile_bf16<4, 4>(acc, P + (size_t)rb * 128 * NP + cb * 128, NP, smem);
.LBB0_744:
	v_mov_b32_e32 v64, v232
	v_lshrrev_b32_e32 v66, 2, v64
	s_waitcnt lgkmcnt(0)
	v_lshrrev_b32_e32 v65, 1, v64
	v_and_b32_e32 v66, 12, v66
	v_and_or_b32 v65, v65, s51, v66
	v_and_b32_e32 v66, 0x4f, v64
	v_mul_lo_u32 v65, v65, s53
	v_cvt_pk_bf16_f32 v44, 0, v44
	v_lshl_add_u32 v65, v66, 1, v65
	ds_write_b16_d16_hi v65, v44
	v_cvt_pk_bf16_f32 v44, 0, v45
	ds_write_b16_d16_hi v65, v44 offset:272
	v_cvt_pk_bf16_f32 v44, 0, v46
	ds_write_b16_d16_hi v65, v44 offset:544
	v_cvt_pk_bf16_f32 v44, 0, v47
	ds_write_b16_d16_hi v65, v44 offset:816
	v_cvt_pk_bf16_f32 v40, 0, v40
	ds_write_b16_d16_hi v65, v40 offset:32
	v_cvt_pk_bf16_f32 v40, 0, v41
	ds_write_b16_d16_hi v65, v40 offset:304
	v_cvt_pk_bf16_f32 v40, 0, v42
	ds_write_b16_d16_hi v65, v40 offset:576
	v_cvt_pk_bf16_f32 v40, 0, v43
	ds_write_b16_d16_hi v65, v40 offset:848
	v_cvt_pk_bf16_f32 v36, 0, v36
	ds_write_b16_d16_hi v65, v36 offset:64
	v_cvt_pk_bf16_f32 v36, 0, v37
	ds_write_b16_d16_hi v65, v36 offset:336
	v_cvt_pk_bf16_f32 v36, 0, v38
	ds_write_b16_d16_hi v65, v36 offset:608
	v_cvt_pk_bf16_f32 v36, 0, v39
	ds_write_b16_d16_hi v65, v36 offset:880
	v_cvt_pk_bf16_f32 v32, 0, v32
	ds_write_b16_d16_hi v65, v32 offset:96
	v_cvt_pk_bf16_f32 v32, 0, v33
	ds_write_b16_d16_hi v65, v32 offset:368
	v_cvt_pk_bf16_f32 v32, 0, v34
	ds_write_b16_d16_hi v65, v32 offset:640
	v_cvt_pk_bf16_f32 v32, 0, v35
	ds_write_b16_d16_hi v65, v32 offset:912
	v_cvt_pk_bf16_f32 v28, 0, v28
	ds_write_b16_d16_hi v65, v28 offset:4352
	v_cvt_pk_bf16_f32 v28, 0, v29
	ds_write_b16_d16_hi v65, v28 offset:4624
	v_cvt_pk_bf16_f32 v28, 0, v30
	ds_write_b16_d16_hi v65, v28 offset:4896
	v_cvt_pk_bf16_f32 v28, 0, v31
	ds_write_b16_d16_hi v65, v28 offset:5168
	v_cvt_pk_bf16_f32 v24, 0, v24
	ds_write_b16_d16_hi v65, v24 offset:4384
	v_cvt_pk_bf16_f32 v24, 0, v25
	ds_write_b16_d16_hi v65, v24 offset:4656
	v_cvt_pk_bf16_f32 v24, 0, v26
	ds_write_b16_d16_hi v65, v24 offset:4928
	v_cvt_pk_bf16_f32 v24, 0, v27
	ds_write_b16_d16_hi v65, v24 offset:5200
	v_cvt_pk_bf16_f32 v20, 0, v20
	ds_write_b16_d16_hi v65, v20 offset:4416
	v_cvt_pk_bf16_f32 v20, 0, v21
	ds_write_b16_d16_hi v65, v20 offset:4688
	v_cvt_pk_bf16_f32 v20, 0, v22
	ds_write_b16_d16_hi v65, v20 offset:4960
	v_cvt_pk_bf16_f32 v20, 0, v23
	ds_write_b16_d16_hi v65, v20 offset:5232
	v_cvt_pk_bf16_f32 v16, 0, v16
	ds_write_b16_d16_hi v65, v16 offset:4448
	v_cvt_pk_bf16_f32 v16, 0, v17
	ds_write_b16_d16_hi v65, v16 offset:4720
	v_cvt_pk_bf16_f32 v16, 0, v18
	ds_write_b16_d16_hi v65, v16 offset:4992
	v_cvt_pk_bf16_f32 v16, 0, v19
	ds_write_b16_d16_hi v65, v16 offset:5264
	v_cvt_pk_bf16_f32 v12, 0, v12
	ds_write_b16_d16_hi v65, v12 offset:8704
	v_cvt_pk_bf16_f32 v12, 0, v13
	ds_write_b16_d16_hi v65, v12 offset:8976
	v_cvt_pk_bf16_f32 v12, 0, v14
	ds_write_b16_d16_hi v65, v12 offset:9248
	v_cvt_pk_bf16_f32 v12, 0, v15
	ds_write_b16_d16_hi v65, v12 offset:9520
	v_cvt_pk_bf16_f32 v8, 0, v8
	ds_write_b16_d16_hi v65, v8 offset:8736
	v_cvt_pk_bf16_f32 v8, 0, v9
	ds_write_b16_d16_hi v65, v8 offset:9008
	v_cvt_pk_bf16_f32 v8, 0, v10
	ds_write_b16_d16_hi v65, v8 offset:9280
	v_cvt_pk_bf16_f32 v8, 0, v11
	ds_write_b16_d16_hi v65, v8 offset:9552
	v_cvt_pk_bf16_f32 v4, 0, v4
	ds_write_b16_d16_hi v65, v4 offset:8768
	v_cvt_pk_bf16_f32 v4, 0, v5
	ds_write_b16_d16_hi v65, v4 offset:9040
	v_cvt_pk_bf16_f32 v4, 0, v6
	ds_write_b16_d16_hi v65, v4 offset:9312
	v_cvt_pk_bf16_f32 v4, 0, v7
	ds_write_b16_d16_hi v65, v4 offset:9584
	v_cvt_pk_bf16_f32 v0, 0, v0
	ds_write_b16_d16_hi v65, v0 offset:8800
	v_cvt_pk_bf16_f32 v0, 0, v1
	ds_write_b16_d16_hi v65, v0 offset:9072
	v_cvt_pk_bf16_f32 v0, 0, v2
	ds_write_b16_d16_hi v65, v0 offset:9344
	v_cvt_pk_bf16_f32 v0, 0, v3
	ds_write_b16_d16_hi v65, v0 offset:9616
	v_cvt_pk_bf16_f32 v0, 0, v60
	ds_write_b16_d16_hi v65, v0 offset:13056
	v_cvt_pk_bf16_f32 v0, 0, v61
	ds_write_b16_d16_hi v65, v0 offset:13328
	v_cvt_pk_bf16_f32 v0, 0, v62
	ds_write_b16_d16_hi v65, v0 offset:13600
	v_cvt_pk_bf16_f32 v0, 0, v63
	ds_write_b16_d16_hi v65, v0 offset:13872
	v_cvt_pk_bf16_f32 v0, 0, v56
	ds_write_b16_d16_hi v65, v0 offset:13088
	v_cvt_pk_bf16_f32 v0, 0, v57
	ds_write_b16_d16_hi v65, v0 offset:13360
	v_cvt_pk_bf16_f32 v0, 0, v58
	ds_write_b16_d16_hi v65, v0 offset:13632
	v_cvt_pk_bf16_f32 v0, 0, v59
	ds_write_b16_d16_hi v65, v0 offset:13904
	v_cvt_pk_bf16_f32 v0, 0, v52
	ds_write_b16_d16_hi v65, v0 offset:13120
	v_cvt_pk_bf16_f32 v0, 0, v53
	ds_write_b16_d16_hi v65, v0 offset:13392
	v_cvt_pk_bf16_f32 v0, 0, v54
	ds_write_b16_d16_hi v65, v0 offset:13664
	v_cvt_pk_bf16_f32 v0, 0, v55
	ds_write_b16_d16_hi v65, v0 offset:13936
	v_cvt_pk_bf16_f32 v0, 0, v48
	ds_write_b16_d16_hi v65, v0 offset:13152
	v_cvt_pk_bf16_f32 v0, 0, v49
	ds_write_b16_d16_hi v65, v0 offset:13424
	v_cvt_pk_bf16_f32 v0, 0, v50
	ds_write_b16_d16_hi v65, v0 offset:13696
	s_lshl_b32 s22, s22, 7
	s_mul_hi_i32 s16, s20, 0x130000
	s_mul_i32 s20, s20, 0x130000
	v_cvt_pk_bf16_f32 v0, 0, v51
	s_add_u32 s24, s40, s20
	ds_write_b16_d16_hi v65, v0 offset:13968
	v_ashrrev_i32_e32 v0, 31, v64
	s_addc_u32 s16, s41, s16
	s_ashr_i32 s23, s22, 31
	v_lshrrev_b32_e32 v0, 28, v0
	s_lshl_b64 s[20:21], s[22:23], 1
	v_add_u32_e32 v0, v64, v0
	s_add_u32 s20, s24, s20
	v_ashrrev_i32_e32 v6, 4, v0
	v_and_b32_e32 v0, -16, v0
	s_addc_u32 s21, s16, s21
	v_sub_u32_e32 v0, v64, v0
	v_lshlrev_b32_e32 v4, 3, v0
	v_mov_b64_e32 v[8:9], s[20:21]
	v_mul_lo_u32 v1, v6, s53
	v_ashrrev_i32_e32 v5, 31, v4
	v_mad_i64_i32 v[6:7], s[20:21], v6, s54, v[8:9]
	v_lshl_add_u64 v[10:11], v[4:5], 1, v[6:7]
	v_add_u32_e32 v4, 0x100, v64
	v_ashrrev_i32_e32 v5, 31, v4
	v_lshrrev_b32_e32 v5, 28, v5
	v_lshl_add_u32 v0, v0, 4, v1
	v_add_u32_e32 v5, v4, v5
	s_waitcnt lgkmcnt(0)
	s_barrier
; template <int WM, int WN>
; __device__ __forceinline__ void store_tile_bf16(const f32x4 (&acc)[WM][WN], u16* dst, int ld, char* smem) {
;     ...
;   constexpr int CPR = BN / 8;
; #pragma unroll
;   for (int i = 0; i < BM * CPR / 256; ++i) {
;     int q = tid + 256 * i, row = q / CPR, c = q % CPR;
;     uint4 v = *reinterpret_cast<const uint4*>(T + row * STR + c * 8);
;     *reinterpret_cast<uint4*>(dst + (size_t)row * ld + c * 8) = v;
;   }
; __device__ void phase_inproj(const Params& p, int layer, char* smem) {
;     ...
;   for (int t = li_; t < rbp_ * 38; t += nl_) {
	ds_read_b128 v[0:3], v0
	v_ashrrev_i32_e32 v12, 4, v5
	v_and_b32_e32 v5, -16, v5
	v_sub_u32_e32 v13, v4, v5
	v_mul_lo_u32 v4, v12, s53
	v_lshl_add_u32 v4, v13, 4, v4
	ds_read_b128 v[4:7], v4
	s_waitcnt lgkmcnt(1)
	global_store_dwordx4 v[10:11], v[0:3], off
	s_add_i32 s55, s55, s61
	s_cmp_lt_i32 s55, s47
	v_lshlrev_b32_e32 v0, 3, v13
	v_ashrrev_i32_e32 v1, 31, v0
	v_mad_i64_i32 v[2:3], s[20:21], v12, s54, v[8:9]
	v_lshl_add_u64 v[0:1], v[0:1], 1, v[2:3]
	s_waitcnt lgkmcnt(0)
	global_store_dwordx4 v[0:1], v[4:7], off
	v_add_u32_e32 v0, 0x200, v64
	v_ashrrev_i32_e32 v1, 31, v0
	v_lshrrev_b32_e32 v1, 28, v1
	v_add_u32_e32 v1, v0, v1
	v_ashrrev_i32_e32 v6, 4, v1
	v_and_b32_e32 v1, -16, v1
	v_sub_u32_e32 v0, v0, v1
	v_lshlrev_b32_e32 v4, 3, v0
	v_mul_lo_u32 v1, v6, s53
	v_ashrrev_i32_e32 v5, 31, v4
	v_mad_i64_i32 v[6:7], s[20:21], v6, s54, v[8:9]
	v_lshl_add_u64 v[10:11], v[4:5], 1, v[6:7]
	v_add_u32_e32 v4, 0x300, v64
	v_ashrrev_i32_e32 v5, 31, v4
	v_lshrrev_b32_e32 v5, 28, v5
	v_lshl_add_u32 v0, v0, 4, v1
	v_add_u32_e32 v5, v4, v5
	ds_read_b128 v[0:3], v0
	v_ashrrev_i32_e32 v12, 4, v5
	v_and_b32_e32 v5, -16, v5
	v_sub_u32_e32 v13, v4, v5
	v_mul_lo_u32 v4, v12, s53
	v_lshl_add_u32 v4, v13, 4, v4
	ds_read_b128 v[4:7], v4
	s_waitcnt lgkmcnt(1)
	global_store_dwordx4 v[10:11], v[0:3], off
	s_nop 1
	v_lshlrev_b32_e32 v0, 3, v13
	v_ashrrev_i32_e32 v1, 31, v0
	v_mad_i64_i32 v[2:3], s[20:21], v12, s54, v[8:9]
	v_lshl_add_u64 v[0:1], v[0:1], 1, v[2:3]
	s_waitcnt lgkmcnt(0)
	global_store_dwordx4 v[0:1], v[4:7], off
	v_add_u32_e32 v0, 0x400, v64
	v_ashrrev_i32_e32 v1, 31, v0
	v_lshrrev_b32_e32 v1, 28, v1
	v_add_u32_e32 v1, v0, v1
	v_ashrrev_i32_e32 v6, 4, v1
	v_and_b32_e32 v1, -16, v1
	v_sub_u32_e32 v0, v0, v1
	v_lshlrev_b32_e32 v4, 3, v0
	v_mul_lo_u32 v1, v6, s53
	v_ashrrev_i32_e32 v5, 31, v4
	v_mad_i64_i32 v[6:7], s[20:21], v6, s54, v[8:9]
	v_lshl_add_u64 v[10:11], v[4:5], 1, v[6:7]
	v_add_u32_e32 v4, 0x500, v64
	v_ashrrev_i32_e32 v5, 31, v4
	v_lshrrev_b32_e32 v5, 28, v5
	v_lshl_add_u32 v0, v0, 4, v1
	v_add_u32_e32 v5, v4, v5
	ds_read_b128 v[0:3], v0
	v_ashrrev_i32_e32 v12, 4, v5
	v_and_b32_e32 v5, -16, v5
	v_sub_u32_e32 v13, v4, v5
	v_mul_lo_u32 v4, v12, s53
	v_lshl_add_u32 v4, v13, 4, v4
	ds_read_b128 v[4:7], v4
	s_waitcnt lgkmcnt(1)
	global_store_dwordx4 v[10:11], v[0:3], off
	s_nop 1
	v_lshlrev_b32_e32 v0, 3, v13
	v_ashrrev_i32_e32 v1, 31, v0
	v_mad_i64_i32 v[2:3], s[20:21], v12, s54, v[8:9]
	v_lshl_add_u64 v[0:1], v[0:1], 1, v[2:3]
	s_waitcnt lgkmcnt(0)
	global_store_dwordx4 v[0:1], v[4:7], off
	v_add_u32_e32 v0, 0x600, v64
	v_ashrrev_i32_e32 v1, 31, v0
	v_lshrrev_b32_e32 v1, 28, v1
	v_add_u32_e32 v1, v0, v1
	v_ashrrev_i32_e32 v6, 4, v1
	v_and_b32_e32 v1, -16, v1
	v_sub_u32_e32 v0, v0, v1
	v_lshlrev_b32_e32 v4, 3, v0
	v_mul_lo_u32 v1, v6, s53
	v_ashrrev_i32_e32 v5, 31, v4
	v_mad_i64_i32 v[6:7], s[20:21], v6, s54, v[8:9]
	v_lshl_add_u64 v[10:11], v[4:5], 1, v[6:7]
	v_add_u32_e32 v4, 0x700, v64
	v_ashrrev_i32_e32 v5, 31, v4
	v_lshrrev_b32_e32 v5, 28, v5
	v_lshl_add_u32 v0, v0, 4, v1
	v_add_u32_e32 v5, v4, v5
	ds_read_b128 v[0:3], v0
	v_ashrrev_i32_e32 v12, 4, v5
	v_and_b32_e32 v5, -16, v5
	v_sub_u32_e32 v13, v4, v5
	v_mul_lo_u32 v4, v12, s53
	v_lshl_add_u32 v4, v13, 4, v4
	ds_read_b128 v[4:7], v4
	s_waitcnt lgkmcnt(1)
	global_store_dwordx4 v[10:11], v[0:3], off
	s_nop 1
	v_lshlrev_b32_e32 v0, 3, v13
	v_ashrrev_i32_e32 v1, 31, v0
	v_mad_i64_i32 v[2:3], s[20:21], v12, s54, v[8:9]
	v_lshl_add_u64 v[0:1], v[0:1], 1, v[2:3]
	s_waitcnt lgkmcnt(0)
	global_store_dwordx4 v[0:1], v[4:7], off
	s_cbranch_scc0 .LBB0_752

; __device__ void phase_inproj(const Params& p, int layer, char* smem) {
;     ...
;     if (cb >= 26 && cb <= 29) {
;       float mx = 0.f;
; #pragma unroll
;       for (int m = 0; m < 4; ++m)
; #pragma unroll
;         for (int j = 0; j < 4; ++j) {
;           float ss = 0.f;
; #pragma unroll
;           for (int n = 0; n < 4; ++n) ss += acc[m][n][j] * acc[m][n][j];
;           ss += __shfl_xor(ss, 1);
;           ss += __shfl_xor(ss, 2);
;           ss += __shfl_xor(ss, 4);
;           ss += __shfl_xor(ss, 8);
;           mx = fmaxf(mx, ss);
;         }
.LBB0_749:
	s_sub_i32 s16, s22, 26
	s_cmp_gt_u32 s16, 3
	s_cbranch_scc1 .LBB0_744
	v_and_b32_e32 v65, 64, v129
	v_xor_b32_e32 v64, 1, v129
	v_add_u32_e32 v65, 64, v65
	v_mul_f32_e32 v66, v44, v44
	v_mul_f32_e32 v71, v45, v45
	v_cmp_lt_i32_e32 vcc, v64, v65
	v_fmac_f32_e32 v66, v40, v40
	v_fmac_f32_e32 v71, v41, v41
	v_mul_f32_e32 v73, v46, v46
	v_mul_f32_e32 v75, v47, v47
	v_cndmask_b32_e32 v64, v129, v64, vcc
	v_fmac_f32_e32 v66, v36, v36
	v_fmac_f32_e32 v71, v37, v37
	v_fmac_f32_e32 v73, v42, v42
	v_fmac_f32_e32 v75, v43, v43
	v_lshlrev_b32_e32 v64, 2, v64
	v_fmac_f32_e32 v66, v32, v32
	v_fmac_f32_e32 v71, v33, v33
	v_fmac_f32_e32 v73, v38, v38
	v_fmac_f32_e32 v75, v39, v39
	ds_bpermute_b32 v67, v64, v66
	ds_bpermute_b32 v72, v64, v71
	v_fmac_f32_e32 v73, v34, v34
	v_fmac_f32_e32 v75, v35, v35
	ds_bpermute_b32 v74, v64, v73
	ds_bpermute_b32 v76, v64, v75
	v_xor_b32_e32 v68, 2, v129
	v_cmp_lt_i32_e32 vcc, v68, v65
	s_waitcnt lgkmcnt(3)
	v_add_f32_e32 v66, v66, v67
	s_waitcnt lgkmcnt(2)
	v_add_f32_e32 v71, v71, v72
	v_cndmask_b32_e32 v68, v129, v68, vcc
	v_lshlrev_b32_e32 v68, 2, v68
	ds_bpermute_b32 v67, v68, v66
	ds_bpermute_b32 v72, v68, v71
	s_waitcnt lgkmcnt(3)
	v_add_f32_e32 v73, v73, v74
	s_waitcnt lgkmcnt(2)
	v_add_f32_e32 v75, v75, v76
	ds_bpermute_b32 v74, v68, v73
	ds_bpermute_b32 v76, v68, v75
	v_xor_b32_e32 v69, 4, v129
	v_cmp_lt_i32_e32 vcc, v69, v65
	s_waitcnt lgkmcnt(3)
	v_add_f32_e32 v66, v66, v67
	s_waitcnt lgkmcnt(2)
	v_add_f32_e32 v71, v71, v72
	v_cndmask_b32_e32 v69, v129, v69, vcc
	v_lshlrev_b32_e32 v69, 2, v69
	ds_bpermute_b32 v67, v69, v66
	ds_bpermute_b32 v72, v69, v71
	s_waitcnt lgkmcnt(3)
	v_add_f32_e32 v73, v73, v74
	s_waitcnt lgkmcnt(2)
	v_add_f32_e32 v75, v75, v76
	ds_bpermute_b32 v74, v69, v73
	ds_bpermute_b32 v76, v69, v75
	v_xor_b32_e32 v70, 8, v129
	v_cmp_lt_i32_e32 vcc, v70, v65
	s_waitcnt lgkmcnt(3)
	v_add_f32_e32 v66, v66, v67
	s_waitcnt lgkmcnt(2)
	v_add_f32_e32 v71, v71, v72
	v_cndmask_b32_e32 v70, v129, v70, vcc
	v_lshlrev_b32_e32 v70, 2, v70
	ds_bpermute_b32 v67, v70, v66
	ds_bpermute_b32 v72, v70, v71
	s_waitcnt lgkmcnt(3)
	v_add_f32_e32 v73, v73, v74
	s_waitcnt lgkmcnt(2)
	v_add_f32_e32 v75, v75, v76
	ds_bpermute_b32 v74, v70, v73
	ds_bpermute_b32 v76, v70, v75
	s_waitcnt lgkmcnt(3)
	v_add_f32_e32 v66, v66, v67
	s_waitcnt lgkmcnt(2)
	v_add_f32_e32 v67, v71, v72
	v_max3_f32 v66, v66, 0, v67
	s_waitcnt lgkmcnt(1)
	v_add_f32_e32 v67, v73, v74
	s_waitcnt lgkmcnt(0)
	v_add_f32_e32 v71, v75, v76
	v_max3_f32 v66, v66, v67, v71
	v_mul_f32_e32 v67, v28, v28
	v_mul_f32_e32 v72, v29, v29
	v_fmac_f32_e32 v67, v24, v24
	v_fmac_f32_e32 v72, v25, v25
	v_mul_f32_e32 v74, v30, v30
	v_fmac_f32_e32 v67, v20, v20
	v_fmac_f32_e32 v72, v21, v21
	v_fmac_f32_e32 v74, v26, v26
	v_fmac_f32_e32 v67, v16, v16
	v_fmac_f32_e32 v72, v17, v17
	v_fmac_f32_e32 v74, v22, v22
	ds_bpermute_b32 v71, v64, v67
	ds_bpermute_b32 v73, v64, v72
	v_fmac_f32_e32 v74, v18, v18
	ds_bpermute_b32 v75, v64, v74
	v_mul_f32_e32 v76, v31, v31
	s_waitcnt lgkmcnt(2)
	v_add_f32_e32 v67, v67, v71
	s_waitcnt lgkmcnt(1)
	v_add_f32_e32 v72, v72, v73
	ds_bpermute_b32 v71, v68, v67
	ds_bpermute_b32 v73, v68, v72
	s_waitcnt lgkmcnt(2)
	v_add_f32_e32 v74, v74, v75
	ds_bpermute_b32 v75, v68, v74
	v_fmac_f32_e32 v76, v27, v27
	s_waitcnt lgkmcnt(2)
	v_add_f32_e32 v67, v67, v71
	s_waitcnt lgkmcnt(1)
	v_add_f32_e32 v72, v72, v73
	ds_bpermute_b32 v71, v69, v67
	ds_bpermute_b32 v73, v69, v72
	s_waitcnt lgkmcnt(2)
	v_add_f32_e32 v74, v74, v75
	ds_bpermute_b32 v75, v69, v74
	v_fmac_f32_e32 v76, v23, v23
	s_waitcnt lgkmcnt(2)
	v_add_f32_e32 v67, v67, v71
	s_waitcnt lgkmcnt(1)
	v_add_f32_e32 v72, v72, v73
	ds_bpermute_b32 v71, v70, v67
	ds_bpermute_b32 v73, v70, v72
	s_waitcnt lgkmcnt(2)
	v_add_f32_e32 v74, v74, v75
	ds_bpermute_b32 v75, v70, v74
	v_fmac_f32_e32 v76, v19, v19
	ds_bpermute_b32 v77, v64, v76
	s_waitcnt lgkmcnt(3)
	v_add_f32_e32 v67, v67, v71
	s_waitcnt lgkmcnt(2)
	v_add_f32_e32 v71, v72, v73
	v_max3_f32 v66, v66, v67, v71
	s_waitcnt lgkmcnt(1)
	v_add_f32_e32 v67, v74, v75
	v_mul_f32_e32 v73, v12, v12
	v_mul_f32_e32 v75, v13, v13
	v_fmac_f32_e32 v73, v8, v8
	v_fmac_f32_e32 v75, v9, v9
	s_waitcnt lgkmcnt(0)
	v_add_f32_e32 v71, v76, v77
	v_fmac_f32_e32 v73, v4, v4
	v_fmac_f32_e32 v75, v5, v5
	ds_bpermute_b32 v72, v68, v71
	v_fmac_f32_e32 v73, v0, v0
	v_fmac_f32_e32 v75, v1, v1
	ds_bpermute_b32 v74, v64, v73
	ds_bpermute_b32 v76, v64, v75
	s_waitcnt lgkmcnt(2)
	v_add_f32_e32 v71, v71, v72
	ds_bpermute_b32 v72, v69, v71
	s_waitcnt lgkmcnt(2)
	v_add_f32_e32 v73, v73, v74
	s_waitcnt lgkmcnt(1)
; __device__ void phase_inproj(const Params& p, int layer, char* smem) {
;     ...
;           ss += __shfl_xor(ss, 1);
;           ss += __shfl_xor(ss, 2);
;           ss += __shfl_xor(ss, 4);
;           ss += __shfl_xor(ss, 8);
;           mx = fmaxf(mx, ss);
;         }
;       mx = fmaxf(mx, __shfl_xor(mx, 16));
;       mx = fmaxf(mx, __shfl_xor(mx, 32));
;       if (lane == 0) {
;         unsigned* km = reinterpret_cast<unsigned*>(wsb(p) + OFF_MISC) + 64 + layer * 16 + (rb >> 7) * 8 + (cb - 26) * 2 + wc;
;         atomicMax(km, __float_as_uint(mx));
;       }
	v_add_f32_e32 v75, v75, v76
	ds_bpermute_b32 v74, v68, v73
	ds_bpermute_b32 v76, v68, v75
	s_waitcnt lgkmcnt(2)
	v_add_f32_e32 v71, v71, v72
	ds_bpermute_b32 v72, v70, v71
	s_waitcnt lgkmcnt(2)
	v_add_f32_e32 v73, v73, v74
	s_waitcnt lgkmcnt(1)
	v_add_f32_e32 v75, v75, v76
	ds_bpermute_b32 v74, v69, v73
	ds_bpermute_b32 v76, v69, v75
	s_waitcnt lgkmcnt(2)
	v_add_f32_e32 v71, v71, v72
	v_max3_f32 v66, v66, v67, v71
	s_waitcnt lgkmcnt(1)
	v_add_f32_e32 v67, v73, v74
	s_waitcnt lgkmcnt(0)
	v_add_f32_e32 v72, v75, v76
	v_mul_f32_e32 v74, v14, v14
	v_mul_f32_e32 v76, v15, v15
	v_fmac_f32_e32 v74, v10, v10
	v_fmac_f32_e32 v76, v11, v11
	v_fmac_f32_e32 v74, v6, v6
	v_fmac_f32_e32 v76, v7, v7
	v_fmac_f32_e32 v74, v2, v2
	v_fmac_f32_e32 v76, v3, v3
	ds_bpermute_b32 v71, v70, v67
	ds_bpermute_b32 v73, v70, v72
	ds_bpermute_b32 v75, v64, v74
	ds_bpermute_b32 v77, v64, v76
	s_waitcnt lgkmcnt(3)
	v_add_f32_e32 v67, v67, v71
	s_waitcnt lgkmcnt(2)
	v_add_f32_e32 v71, v72, v73
	s_waitcnt lgkmcnt(1)
	v_add_f32_e32 v72, v74, v75
	s_waitcnt lgkmcnt(0)
	v_add_f32_e32 v74, v76, v77
	v_mul_f32_e32 v76, v60, v60
	v_fmac_f32_e32 v76, v56, v56
	v_fmac_f32_e32 v76, v52, v52
	ds_bpermute_b32 v73, v68, v72
	ds_bpermute_b32 v75, v68, v74
	v_fmac_f32_e32 v76, v48, v48
	ds_bpermute_b32 v77, v64, v76
	v_max3_f32 v66, v66, v67, v71
	s_waitcnt lgkmcnt(2)
	v_add_f32_e32 v72, v72, v73
	s_waitcnt lgkmcnt(1)
	v_add_f32_e32 v74, v74, v75
	ds_bpermute_b32 v73, v69, v72
	ds_bpermute_b32 v75, v69, v74
	s_waitcnt lgkmcnt(2)
	v_add_f32_e32 v76, v76, v77
	ds_bpermute_b32 v77, v68, v76
	s_waitcnt lgkmcnt(2)
	v_add_f32_e32 v72, v72, v73
	s_waitcnt lgkmcnt(1)
	v_add_f32_e32 v74, v74, v75
	ds_bpermute_b32 v73, v70, v72
	ds_bpermute_b32 v75, v70, v74
	s_waitcnt lgkmcnt(2)
	v_add_f32_e32 v76, v76, v77
	ds_bpermute_b32 v77, v69, v76
	s_waitcnt lgkmcnt(2)
	v_add_f32_e32 v67, v72, v73
	s_waitcnt lgkmcnt(1)
	v_add_f32_e32 v71, v74, v75
	v_mul_f32_e32 v72, v61, v61
	v_max3_f32 v66, v66, v67, v71
	s_waitcnt lgkmcnt(0)
	v_add_f32_e32 v67, v76, v77
	v_fmac_f32_e32 v72, v57, v57
	v_mul_f32_e32 v74, v62, v62
	v_mul_f32_e32 v76, v63, v63
	v_fmac_f32_e32 v72, v53, v53
	v_fmac_f32_e32 v74, v58, v58
	v_fmac_f32_e32 v76, v59, v59
	v_fmac_f32_e32 v72, v49, v49
	v_fmac_f32_e32 v74, v54, v54
	v_fmac_f32_e32 v76, v55, v55
	ds_bpermute_b32 v73, v64, v72
	v_fmac_f32_e32 v74, v50, v50
	v_fmac_f32_e32 v76, v51, v51
	ds_bpermute_b32 v75, v64, v74
	ds_bpermute_b32 v64, v64, v76
	s_waitcnt lgkmcnt(2)
	v_add_f32_e32 v72, v72, v73
	ds_bpermute_b32 v73, v68, v72
	ds_bpermute_b32 v71, v70, v67
	s_waitcnt lgkmcnt(3)
	v_add_f32_e32 v74, v74, v75
	s_waitcnt lgkmcnt(2)
	v_add_f32_e32 v64, v76, v64
	ds_bpermute_b32 v75, v68, v74
	ds_bpermute_b32 v68, v68, v64
	s_waitcnt lgkmcnt(3)
	v_add_f32_e32 v72, v72, v73
	ds_bpermute_b32 v73, v69, v72
	s_waitcnt lgkmcnt(3)
	v_add_f32_e32 v67, v67, v71
	s_waitcnt lgkmcnt(2)
	v_add_f32_e32 v74, v74, v75
	s_waitcnt lgkmcnt(1)
	v_add_f32_e32 v64, v64, v68
	ds_bpermute_b32 v75, v69, v74
	ds_bpermute_b32 v68, v69, v64
	s_waitcnt lgkmcnt(2)
	v_add_f32_e32 v69, v72, v73
	ds_bpermute_b32 v72, v70, v69
	s_waitcnt lgkmcnt(2)
	v_add_f32_e32 v73, v74, v75
	s_waitcnt lgkmcnt(1)
	v_add_f32_e32 v64, v64, v68
	ds_bpermute_b32 v74, v70, v73
	ds_bpermute_b32 v68, v70, v64
	s_waitcnt lgkmcnt(2)
	v_add_f32_e32 v69, v69, v72
	v_max3_f32 v66, v66, v67, v69
	s_waitcnt lgkmcnt(1)
	v_add_f32_e32 v67, v73, v74
	s_waitcnt lgkmcnt(0)
	v_add_f32_e32 v64, v64, v68
	v_max3_f32 v64, v66, v67, v64
	v_xor_b32_e32 v66, 16, v129
	v_cmp_lt_i32_e32 vcc, v66, v65
	s_nop 1
	v_cndmask_b32_e32 v66, v129, v66, vcc
	v_lshlrev_b32_e32 v66, 2, v66
	ds_bpermute_b32 v66, v66, v64
	s_waitcnt lgkmcnt(0)
	v_max_f32_e32 v64, v64, v66
	v_xor_b32_e32 v66, 32, v129
	v_cmp_lt_i32_e32 vcc, v66, v65
	s_nop 1
	v_cndmask_b32_e32 v65, v129, v66, vcc
	v_lshlrev_b32_e32 v65, 2, v65
	ds_bpermute_b32 v65, v65, v64
	s_and_saveexec_b64 s[24:25], s[12:13]
	s_cbranch_execz .LBB0_743
	s_waitcnt lgkmcnt(0)
	v_max_f32_e32 v66, v64, v65
	v_mov_b32_e32 v64, v117
	v_mov_b32_e32 v119, v117
	v_readfirstlane_b32 s16, v64
	s_ashr_i32 s21, s16, 31
	s_add_u32 s16, s28, s16
	s_addc_u32 s21, s29, s21
	s_ashr_i32 s23, s20, 4
	s_and_b32 s26, s23, -8
	s_ashr_i32 s27, s26, 31
	s_lshl_b64 s[26:27], s[26:27], 2
	s_add_u32 s23, s16, s26
	s_addc_u32 s21, s21, s27
	s_lshl_b32 s16, s22, 1
	s_lshl_b64 s[26:27], s[16:17], 2
	s_add_u32 s26, s23, s26
	s_addc_u32 s27, s21, s27
	v_lshl_add_u64 v[64:65], s[26:27], 0, v[118:119]
	v_add_co_u32_e32 v64, vcc, 0x1e8a4000, v64
	s_nop 1
	v_addc_co_u32_e32 v65, vcc, 0, v65, vcc
	global_atomic_umax v[64:65], v66, off offset:2224
	s_branch .LBB0_743

; template <int DH, int MODE>
; __device__ void attn_item(const Params& p, int layer, int b, int blk, int head, char* smem) {
;     ...
;   {
;     constexpr int OST = DH + 4;
;     constexpr int CPR = DH / 8;
;     constexpr int NCH = 128 * CPR / 256;
;     float* Of = reinterpret_cast<float*>(smem);
;     uint4 gt[NCH];
; #pragma unroll
;     for (int i = 0; i < NCH; ++i) {
;       int q = tid + 256 * i, r = q / CPR, c = (q % CPR) * 8;
;       gt[i] = *reinterpret_cast<const uint4*>(P + (tq0 + r) * NP + gcol + c);
;     }
;     float lis[2][4];
; #pragma unroll
;     for (int m = 0; m < 2; ++m)
; #pragma unroll
;       for (int j = 0; j < 4; ++j) lis[m][j] = (MODE == 0) ? linv_s[wid * 32 + m * 16 + fq * 4 + j] : 1.f;
;     if (MODE == 0) __syncthreads();
; #pragma unroll
;     for (int m = 0; m < 2; ++m)
; #pragma unroll
;       for (int j = 0; j < 4; ++j) {
;         int r = wid * 32 + m * 16 + fq * 4 + j;
; #pragma unroll
;         for (int n = 0; n < NDT; ++n) Of[r * OST + n * 16 + fr] = o[m][n][j] * lis[m][j];
;       }
.LBB0_791:
	s_ashr_i32 s13, s86, 31
	s_add_u32 s12, s28, s86
	s_addc_u32 s13, s29, s13
	s_lshl_b32 s14, s83, 1
	s_add_u32 s16, s48, s14
	s_addc_u32 s17, s49, 0
	v_lshl_add_u64 v[2:3], s[20:21], 0, v[134:135]
	v_mov_b64_e32 v[4:5], s[16:17]
	v_mad_u64_u32 v[0:1], s[16:17], v2, s45, v[4:5]
	v_mad_i32_i24 v1, v3, s45, v1
	s_waitcnt vmcnt(12)
	v_lshl_add_u64 v[76:77], v[0:1], 0, v[138:139]
	v_add_u32_e32 v0, 0x100, v161
	v_ashrrev_i32_e32 v1, 31, v0
	v_lshrrev_b32_e32 v1, 28, v1
	v_add_u32_e32 v1, v0, v1
	v_ashrrev_i32_e32 v8, 4, v1
	v_and_b32_e32 v1, -16, v1
	s_waitcnt vmcnt(5)
	v_sub_u32_e32 v99, v0, v1
	v_lshlrev_b32_e32 v0, 3, v99
	v_ashrrev_i32_e32 v1, 31, v0
	s_waitcnt vmcnt(3)
	v_lshlrev_b64 v[92:93], 1, v[0:1]
	v_add_u32_e32 v0, 0x200, v161
	v_ashrrev_i32_e32 v1, 31, v0
	v_lshrrev_b32_e32 v1, 28, v1
	v_add_u32_e32 v1, v0, v1
	v_ashrrev_i32_e32 v9, 31, v8
	v_ashrrev_i32_e32 v94, 4, v1
	v_and_b32_e32 v1, -16, v1
	v_lshl_add_u64 v[10:11], s[20:21], 0, v[8:9]
	v_sub_u32_e32 v9, v0, v1
	v_lshlrev_b32_e32 v0, 3, v9
	v_ashrrev_i32_e32 v1, 31, v0
	v_lshlrev_b64 v[100:101], 1, v[0:1]
	v_add_u32_e32 v0, 0x300, v161
	v_ashrrev_i32_e32 v1, 31, v0
	v_lshrrev_b32_e32 v1, 28, v1
	v_add_u32_e32 v1, v0, v1
	v_ashrrev_i32_e32 v102, 4, v1
	v_and_b32_e32 v1, -16, v1
	v_sub_u32_e32 v128, v0, v1
	v_lshlrev_b32_e32 v0, 3, v128
	v_ashrrev_i32_e32 v1, 31, v0
	s_waitcnt vmcnt(0)
	v_lshlrev_b64 v[106:107], 1, v[0:1]
	v_add_u32_e32 v0, 0x400, v161
	v_ashrrev_i32_e32 v1, 31, v0
	v_lshrrev_b32_e32 v1, 28, v1
	v_add_u32_e32 v1, v0, v1
	v_ashrrev_i32_e32 v103, 31, v102
	v_ashrrev_i32_e32 v108, 4, v1
	v_and_b32_e32 v1, -16, v1
	v_lshl_add_u64 v[104:105], s[20:21], 0, v[102:103]
	v_sub_u32_e32 v103, v0, v1
	v_lshlrev_b32_e32 v0, 3, v103
	v_ashrrev_i32_e32 v1, 31, v0
	v_lshlrev_b64 v[112:113], 1, v[0:1]
	v_add_u32_e32 v0, 0x500, v161
	v_ashrrev_i32_e32 v1, 31, v0
	v_lshrrev_b32_e32 v1, 28, v1
	v_add_u32_e32 v1, v0, v1
	v_ashrrev_i32_e32 v109, 31, v108
	v_ashrrev_i32_e32 v114, 4, v1
	v_and_b32_e32 v1, -16, v1
	v_mad_u64_u32 v[6:7], s[16:17], v10, s45, v[4:5]
	v_ashrrev_i32_e32 v95, 31, v94
	v_lshl_add_u64 v[110:111], s[20:21], 0, v[108:109]
	v_sub_u32_e32 v109, v0, v1
	v_mad_i32_i24 v7, v11, s45, v7
	v_lshl_add_u64 v[96:97], s[20:21], 0, v[94:95]
	v_lshlrev_b32_e32 v0, 3, v109
	v_lshl_add_u64 v[78:79], v[6:7], 0, v[92:93]
	v_mad_u64_u32 v[6:7], s[16:17], v96, s45, v[4:5]
	v_ashrrev_i32_e32 v1, 31, v0
	v_mad_i32_i24 v7, v97, s45, v7
	v_lshlrev_b64 v[118:119], 1, v[0:1]
	v_add_u32_e32 v0, 0x600, v161
	v_lshl_add_u64 v[80:81], v[6:7], 0, v[100:101]
	v_mad_u64_u32 v[6:7], s[16:17], v104, s45, v[4:5]
	v_ashrrev_i32_e32 v1, 31, v0
	v_mad_i32_i24 v7, v105, s45, v7
	v_lshrrev_b32_e32 v1, 28, v1
	v_lshl_add_u64 v[82:83], v[6:7], 0, v[106:107]
	v_mad_u64_u32 v[6:7], s[16:17], v110, s45, v[4:5]
	v_ashrrev_i32_e32 v115, 31, v114
	v_add_u32_e32 v1, v0, v1
	v_mad_i32_i24 v7, v111, s45, v7
	v_lshl_add_u64 v[116:117], s[20:21], 0, v[114:115]
	v_ashrrev_i32_e32 v120, 4, v1
	v_and_b32_e32 v1, -16, v1
	v_lshl_add_u64 v[84:85], v[6:7], 0, v[112:113]
	v_mad_u64_u32 v[6:7], s[16:17], v116, s45, v[4:5]
	v_sub_u32_e32 v115, v0, v1
	v_ashrrev_i32_e32 v121, 31, v120
	v_mad_i32_i24 v7, v117, s45, v7
	v_lshlrev_b32_e32 v0, 3, v115
	v_lshl_add_u64 v[122:123], s[20:21], 0, v[120:121]
	v_lshl_add_u64 v[86:87], v[6:7], 0, v[118:119]
	v_mad_u64_u32 v[6:7], s[16:17], v122, s45, v[4:5]
	v_ashrrev_i32_e32 v1, 31, v0
	v_mad_i32_i24 v7, v123, s45, v7
	v_lshlrev_b64 v[124:125], 1, v[0:1]
	v_lshl_add_u64 v[0:1], v[6:7], 0, v[124:125]
	v_add_u32_e32 v6, 0x700, v161
	v_ashrrev_i32_e32 v7, 31, v6
	v_lshrrev_b32_e32 v7, 28, v7
	v_add_u32_e32 v7, v6, v7
	v_ashrrev_i32_e32 v126, 4, v7
	v_and_b32_e32 v7, -16, v7
	v_sub_u32_e32 v121, v6, v7
	v_lshlrev_b32_e32 v6, 3, v121
	v_ashrrev_i32_e32 v127, 31, v126
	v_lshl_add_u64 v[88:89], s[20:21], 0, v[126:127]
	v_ashrrev_i32_e32 v7, 31, v6
	v_mad_u64_u32 v[4:5], s[16:17], v88, s45, v[4:5]
	v_lshlrev_b64 v[90:91], 1, v[6:7]
	v_lshl_or_b32 v6, v137, 2, v130
	v_mad_i32_i24 v5, v89, s45, v5
	v_mul_lo_u32 v6, v6, s69
	v_lshl_add_u64 v[4:5], v[4:5], 0, v[90:91]
	v_lshl_add_u32 v95, v162, 2, v6
	s_barrier
	ds_write2_b32 v95, v12, v48 offset1:16
	ds_write2_b32 v95, v52, v56 offset0:32 offset1:48
	ds_write2_b32 v95, v60, v64 offset0:64 offset1:80
	ds_write2_b32 v95, v68, v72 offset0:96 offset1:112
	ds_write2_b32 v95, v13, v49 offset0:132 offset1:148
	ds_write2_b32 v95, v53, v57 offset0:164 offset1:180
	ds_write2_b32 v95, v61, v65 offset0:196 offset1:212
	ds_write2_b32 v95, v69, v73 offset0:228 offset1:244
	v_add_u32_e32 v12, 0x400, v95
	v_add_co_u32_e32 v4, vcc, s80, v4
	ds_write2_b32 v12, v14, v50 offset0:8 offset1:24
	ds_write2_b32 v12, v54, v58 offset0:40 offset1:56
	v_addc_co_u32_e32 v5, vcc, 0, v5, vcc
	global_load_dwordx4 v[4:7], v[4:5], off offset:512
	ds_write2_b32 v12, v62, v66 offset0:72 offset1:88
	ds_write2_b32 v12, v70, v74 offset0:104 offset1:120
	ds_write2_b32 v12, v15, v51 offset0:140 offset1:156
	ds_write2_b32 v12, v55, v59 offset0:172 offset1:188
	ds_write2_b32 v12, v63, v67 offset0:204 offset1:220
	ds_write2_b32 v12, v71, v75 offset0:236 offset1:252
	v_add_u32_e32 v12, 0x2000, v95
	ds_write2_b32 v12, v16, v20 offset0:64 offset1:80
	ds_write2_b32 v12, v24, v36 offset0:96 offset1:112
	ds_write2_b32 v12, v28, v40 offset0:128 offset1:144
	ds_write2_b32 v12, v44, v32 offset0:160 offset1:176
	ds_write2_b32 v12, v17, v21 offset0:196 offset1:212
	ds_write2_b32 v12, v25, v37 offset0:228 offset1:244
	v_add_u32_e32 v12, 0x2400, v95
	s_add_u32 s12, s12, s14
	ds_write2_b32 v12, v29, v41 offset0:4 offset1:20
	ds_write2_b32 v12, v45, v33 offset0:36 offset1:52
; __device__ __forceinline__ unsigned pack2(float a, float b) { return (unsigned)f2bf(a) | ((unsigned)f2bf(b) << 16); }
; __device__ __forceinline__ float bflo(unsigned w) { return __uint_as_float(w << 16); }
; __device__ __forceinline__ float bfhi(unsigned w) { return __uint_as_float(w & 0xffff0000u); }
; __device__ __forceinline__ float silu_f(float g) { return g / (1.f + __expf(-g)); }
; template <int DH, int MODE>
; __device__ void attn_item(const Params& p, int layer, int b, int blk, int head, char* smem) {
;     ...
;     float* Of = reinterpret_cast<float*>(smem);
;     uint4 gt[NCH];
; #pragma unroll
;     for (int i = 0; i < NCH; ++i) {
;       int q = tid + 256 * i, r = q / CPR, c = (q % CPR) * 8;
;       gt[i] = *reinterpret_cast<const uint4*>(P + (tq0 + r) * NP + gcol + c);
;     }
;     float lis[2][4];
; #pragma unroll
;     for (int m = 0; m < 2; ++m)
; #pragma unroll
;       for (int j = 0; j < 4; ++j) lis[m][j] = (MODE == 0) ? linv_s[wid * 32 + m * 16 + fq * 4 + j] : 1.f;
;     if (MODE == 0) __syncthreads();
; #pragma unroll
;     for (int m = 0; m < 2; ++m)
; #pragma unroll
;       for (int j = 0; j < 4; ++j) {
;         int r = wid * 32 + m * 16 + fq * 4 + j;
; #pragma unroll
;         for (int n = 0; n < NDT; ++n) Of[r * OST + n * 16 + fr] = o[m][n][j] * lis[m][j];
;       }
;     __syncthreads();
; #pragma unroll
;     for (int i = 0; i < NCH; ++i) {
;       int q = tid + 256 * i, r = q / CPR, c = (q % CPR) * 8;
;       float4 m0 = *reinterpret_cast<const float4*>(Of + r * OST + c);
;       float4 m1 = *reinterpret_cast<const float4*>(Of + r * OST + c + 4);
;       float mm[8] = {m0.x, m0.y, m0.z, m0.w, m1.x, m1.y, m1.z, m1.w};
;       unsigned gw[4] = {gt[i].x, gt[i].y, gt[i].z, gt[i].w};
;       unsigned ow[4];
; #pragma unroll
;       for (int e = 0; e < 4; ++e)
;         ow[e] = pack2(mm[2 * e] * silu_f(bflo(gw[e])), mm[2 * e + 1] * silu_f(bfhi(gw[e])));
	ds_write2_b32 v12, v18, v22 offset0:72 offset1:88
	ds_write2_b32 v12, v26, v38 offset0:104 offset1:120
	ds_write2_b32 v12, v30, v42 offset0:136 offset1:152
	ds_write2_b32 v12, v46, v34 offset0:168 offset1:184
	ds_write2_b32 v12, v19, v23 offset0:204 offset1:220
	ds_write2_b32 v12, v27, v39 offset0:236 offset1:252
	v_add_u32_e32 v12, 0x2800, v95
	s_addc_u32 s13, s13, 0
	ds_write2_b32 v12, v31, v43 offset0:12 offset1:28
	ds_write2_b32 v12, v47, v35 offset0:44 offset1:60
	v_mul_lo_u32 v12, v134, s69
	v_mov_b64_e32 v[14:15], s[12:13]
	v_lshl_add_u32 v98, v136, 2, v12
	v_mad_u64_u32 v[12:13], s[12:13], v2, s70, v[14:15]
	v_mul_lo_u32 v2, v8, s69
	v_mad_i32_i24 v13, v3, s70, v13
	v_lshl_add_u32 v95, v99, 5, v2
	v_mad_u64_u32 v[2:3], s[12:13], v10, s70, v[14:15]
	v_mad_i32_i24 v3, v11, s70, v3
	v_lshl_add_u64 v[26:27], v[2:3], 0, v[92:93]
	v_mul_lo_u32 v2, v94, s69
	v_lshl_add_u32 v93, v9, 5, v2
	v_mad_u64_u32 v[2:3], s[12:13], v96, s70, v[14:15]
	v_mad_i32_i24 v3, v97, s70, v3
	v_lshl_add_u64 v[20:21], v[2:3], 0, v[100:101]
	v_mul_lo_u32 v2, v102, s69
	v_lshl_add_u32 v92, v128, 5, v2
	v_mad_u64_u32 v[2:3], s[12:13], v104, s70, v[14:15]
	v_mad_i32_i24 v3, v105, s70, v3
	v_lshl_add_u64 v[16:17], v[2:3], 0, v[106:107]
	v_mul_lo_u32 v2, v108, s69
	v_lshl_add_u32 v75, v103, 5, v2
	v_mad_u64_u32 v[2:3], s[12:13], v110, s70, v[14:15]
	v_mad_i32_i24 v3, v111, s70, v3
	v_lshl_add_u64 v[30:31], v[12:13], 0, v[138:139]
	v_lshl_add_u64 v[12:13], v[2:3], 0, v[112:113]
	v_mul_lo_u32 v2, v114, s69
	v_lshl_add_u32 v74, v109, 5, v2
	v_mad_u64_u32 v[2:3], s[12:13], v116, s70, v[14:15]
	v_mad_i32_i24 v3, v117, s70, v3
	v_lshl_add_u64 v[10:11], v[2:3], 0, v[118:119]
	v_mul_lo_u32 v2, v120, s69
	v_lshl_add_u32 v73, v115, 5, v2
	v_mad_u64_u32 v[2:3], s[12:13], v122, s70, v[14:15]
	v_mad_i32_i24 v3, v123, s70, v3
	v_add_co_u32_e32 v0, vcc, s80, v0
	v_lshl_add_u64 v[8:9], v[2:3], 0, v[124:125]
	v_mul_lo_u32 v2, v126, s69
	v_addc_co_u32_e32 v1, vcc, 0, v1, vcc
	v_lshl_add_u32 v72, v121, 5, v2
	global_load_dwordx4 v[0:3], v[0:1], off offset:512
	v_mad_u64_u32 v[14:15], s[12:13], v88, s70, v[14:15]
	v_mad_i32_i24 v15, v89, s70, v15
	v_lshl_add_u64 v[14:15], v[14:15], 0, v[90:91]
	s_waitcnt vmcnt(1)
	v_lshlrev_b32_e32 v22, 16, v5
	v_lshlrev_b32_e32 v23, 16, v4
	v_mul_f32_e32 v18, 0xbfb8aa3b, v23
	v_mul_f32_e32 v19, 0xbfb8aa3b, v22
	v_exp_f32_e32 v18, v18
	v_exp_f32_e32 v19, v19
	v_and_b32_e32 v24, 0xffff0000, v5
	v_and_b32_e32 v28, 0xffff0000, v4
	v_mul_f32_e32 v4, 0xbfb8aa3b, v28
	v_pk_add_f32 v[18:19], v[18:19], 1.0 op_sel_hi:[1,0]
	v_exp_f32_e32 v4, v4
	v_and_b32_e32 v34, 0xffff0000, v6
	v_rcp_f32_e32 v19, v19
	s_nop 0
	v_mul_f32_e32 v19, v22, v19
	v_mul_f32_e32 v5, 0xbfb8aa3b, v24
	v_exp_f32_e32 v5, v5
	s_nop 0
	v_pk_add_f32 v[4:5], v[4:5], 1.0 op_sel_hi:[1,0]
	v_rcp_f32_e32 v18, v18
	s_nop 0
	v_mul_f32_e32 v18, v23, v18
	v_lshlrev_b32_e32 v33, 16, v6
	v_rcp_f32_e32 v23, v5
	s_nop 0
	v_mul_f32_e32 v23, v24, v23
	v_lshlrev_b32_e32 v32, 16, v7
	v_mul_f32_e32 v24, 0xbfb8aa3b, v33
	v_mul_f32_e32 v25, 0xbfb8aa3b, v32
	v_exp_f32_e32 v24, v24
	v_exp_f32_e32 v25, v25
	v_rcp_f32_e32 v22, v4
	s_nop 0
	v_mul_f32_e32 v22, v28, v22
	v_and_b32_e32 v28, 0xffff0000, v7
	v_pk_add_f32 v[4:5], v[24:25], 1.0 op_sel_hi:[1,0]
	v_mul_f32_e32 v6, 0xbfb8aa3b, v34
	v_exp_f32_e32 v6, v6
	s_waitcnt vmcnt(0)
	v_lshlrev_b32_e32 v40, 16, v3
	v_lshlrev_b32_e32 v41, 16, v2
	v_rcp_f32_e32 v25, v5
	s_nop 0
	v_mul_f32_e32 v25, v32, v25
	v_mul_f32_e32 v7, 0xbfb8aa3b, v28
	v_exp_f32_e32 v7, v7
	s_nop 0
	v_pk_add_f32 v[6:7], v[6:7], 1.0 op_sel_hi:[1,0]
	v_rcp_f32_e32 v24, v4
	s_nop 0
	v_mul_f32_e32 v24, v33, v24
	v_rcp_f32_e32 v29, v7
	s_nop 0
	v_mul_f32_e32 v29, v28, v29
	v_lshlrev_b32_e32 v32, 16, v1
	v_lshlrev_b32_e32 v36, 16, v0
	v_mul_f32_e32 v4, 0xbfb8aa3b, v36
	v_mul_f32_e32 v5, 0xbfb8aa3b, v32
	v_exp_f32_e32 v4, v4
	v_exp_f32_e32 v5, v5
	v_rcp_f32_e32 v28, v6
	s_nop 0
	v_mul_f32_e32 v28, v34, v28
	v_and_b32_e32 v6, 0xffff0000, v1
	v_pk_add_f32 v[4:5], v[4:5], 1.0 op_sel_hi:[1,0]
	v_and_b32_e32 v34, 0xffff0000, v0
	v_mul_f32_e32 v0, 0xbfb8aa3b, v34
	v_exp_f32_e32 v0, v0
	v_and_b32_e32 v42, 0xffff0000, v3
	v_rcp_f32_e32 v33, v5
	s_nop 0
	v_mul_f32_e32 v33, v32, v33
	v_mul_f32_e32 v1, 0xbfb8aa3b, v6
	v_exp_f32_e32 v1, v1
	s_nop 0
	v_pk_add_f32 v[0:1], v[0:1], 1.0 op_sel_hi:[1,0]
	v_rcp_f32_e32 v32, v4
	s_nop 0
	v_mul_f32_e32 v32, v36, v32
	v_rcp_f32_e32 v35, v1
	s_nop 0
	v_mul_f32_e32 v35, v6, v35
	v_add_co_u32_e64 v4, s[12:13], s80, v86
	s_nop 0
	s_nop 0
	v_addc_co_u32_e64 v5, s[12:13], 0, v87, s[12:13]
	global_load_dwordx4 v[4:7], v[4:5], off offset:512
	v_mul_f32_e32 v36, 0xbfb8aa3b, v41
	v_mul_f32_e32 v37, 0xbfb8aa3b, v40
	v_exp_f32_e32 v36, v36
	v_exp_f32_e32 v37, v37
	v_rcp_f32_e32 v1, v0
	s_nop 0
	v_mul_f32_e32 v34, v34, v1
	v_and_b32_e32 v43, 0xffff0000, v2
	v_pk_add_f32 v[0:1], v[36:37], 1.0 op_sel_hi:[1,0]
	v_mul_f32_e32 v2, 0xbfb8aa3b, v43
	v_exp_f32_e32 v2, v2
	v_rcp_f32_e32 v37, v1
	s_nop 0
	v_mul_f32_e32 v37, v40, v37
	v_mul_f32_e32 v3, 0xbfb8aa3b, v42
	v_exp_f32_e32 v3, v3
	s_nop 0
	v_pk_add_f32 v[38:39], v[2:3], 1.0 op_sel_hi:[1,0]
	v_rcp_f32_e32 v36, v0
	s_nop 0
	v_mul_f32_e32 v36, v41, v36
	v_rcp_f32_e32 v39, v39
	s_nop 0
	v_mul_f32_e32 v39, v42, v39
	v_add_co_u32_e64 v0, s[12:13], s80, v84
	s_waitcnt vmcnt(0)
; __device__ __forceinline__ unsigned pack2(float a, float b) { return (unsigned)f2bf(a) | ((unsigned)f2bf(b) << 16); }
; __device__ __forceinline__ float bflo(unsigned w) { return __uint_as_float(w << 16); }
; __device__ __forceinline__ float bfhi(unsigned w) { return __uint_as_float(w & 0xffff0000u); }
; __device__ __forceinline__ float silu_f(float g) { return g / (1.f + __expf(-g)); }
; template <int DH, int MODE>
; __device__ void attn_item(const Params& p, int layer, int b, int blk, int head, char* smem) {
;     ...
;     for (int i = 0; i < NCH; ++i) {
;       int q = tid + 256 * i, r = q / CPR, c = (q % CPR) * 8;
;       float4 m0 = *reinterpret_cast<const float4*>(Of + r * OST + c);
;       float4 m1 = *reinterpret_cast<const float4*>(Of + r * OST + c + 4);
;       float mm[8] = {m0.x, m0.y, m0.z, m0.w, m1.x, m1.y, m1.z, m1.w};
;       unsigned gw[4] = {gt[i].x, gt[i].y, gt[i].z, gt[i].w};
;       unsigned ow[4];
; #pragma unroll
;       for (int e = 0; e < 4; ++e)
;         ow[e] = pack2(mm[2 * e] * silu_f(bflo(gw[e])), mm[2 * e + 1] * silu_f(bfhi(gw[e])));
	v_lshlrev_b32_e32 v46, 16, v5
	v_lshlrev_b32_e32 v47, 16, v4
	v_mul_f32_e32 v40, 0xbfb8aa3b, v47
	v_mul_f32_e32 v41, 0xbfb8aa3b, v46
	v_exp_f32_e32 v40, v40
	v_exp_f32_e32 v41, v41
	v_addc_co_u32_e64 v1, s[12:13], 0, v85, s[12:13]
	v_rcp_f32_e32 v38, v38
	s_nop 0
	v_mul_f32_e32 v38, v43, v38
	v_pk_add_f32 v[40:41], v[40:41], 1.0 op_sel_hi:[1,0]
	v_and_b32_e32 v42, 0xffff0000, v5
	global_load_dwordx4 v[0:3], v[0:1], off offset:512
	v_and_b32_e32 v48, 0xffff0000, v4
	v_mul_f32_e32 v4, 0xbfb8aa3b, v48
	v_rcp_f32_e32 v41, v41
	s_nop 0
	v_mul_f32_e32 v41, v46, v41
	v_exp_f32_e32 v4, v4
	v_mul_f32_e32 v5, 0xbfb8aa3b, v42
	v_exp_f32_e32 v5, v5
	s_nop 0
	v_pk_add_f32 v[4:5], v[4:5], 1.0 op_sel_hi:[1,0]
	v_rcp_f32_e32 v40, v40
	s_nop 0
	v_mul_f32_e32 v40, v47, v40
	v_lshlrev_b32_e32 v49, 16, v6
	v_rcp_f32_e32 v43, v5
	s_nop 0
	v_mul_f32_e32 v43, v42, v43
	v_lshlrev_b32_e32 v46, 16, v7
	v_mul_f32_e32 v44, 0xbfb8aa3b, v49
	v_mul_f32_e32 v45, 0xbfb8aa3b, v46
	v_exp_f32_e32 v44, v44
	v_exp_f32_e32 v45, v45
	v_rcp_f32_e32 v42, v4
	s_nop 0
	v_mul_f32_e32 v42, v48, v42
	v_and_b32_e32 v47, 0xffff0000, v7
	v_pk_add_f32 v[4:5], v[44:45], 1.0 op_sel_hi:[1,0]
	v_and_b32_e32 v48, 0xffff0000, v6
	v_mul_f32_e32 v6, 0xbfb8aa3b, v48
	v_exp_f32_e32 v6, v6
	v_rcp_f32_e32 v45, v5
	s_nop 0
	v_mul_f32_e32 v45, v46, v45
	v_mul_f32_e32 v7, 0xbfb8aa3b, v47
	v_exp_f32_e32 v7, v7
	s_nop 0
	v_pk_add_f32 v[6:7], v[6:7], 1.0 op_sel_hi:[1,0]
	v_rcp_f32_e32 v44, v4
	s_nop 0
	v_mul_f32_e32 v44, v49, v44
	v_rcp_f32_e32 v4, v7
	s_nop 0
	v_mul_f32_e32 v47, v47, v4
	s_waitcnt vmcnt(0)
	v_lshlrev_b32_e32 v50, 16, v1
	v_lshlrev_b32_e32 v51, 16, v0
	v_mul_f32_e32 v4, 0xbfb8aa3b, v51
	v_mul_f32_e32 v5, 0xbfb8aa3b, v50
	v_exp_f32_e32 v4, v4
	v_exp_f32_e32 v5, v5
	v_rcp_f32_e32 v46, v6
	s_nop 0
	v_mul_f32_e32 v46, v48, v46
	v_and_b32_e32 v6, 0xffff0000, v1
	v_pk_add_f32 v[4:5], v[4:5], 1.0 op_sel_hi:[1,0]
	v_and_b32_e32 v54, 0xffff0000, v0
	v_mul_f32_e32 v0, 0xbfb8aa3b, v54
	v_exp_f32_e32 v0, v0
	v_lshlrev_b32_e32 v58, 16, v2
	v_rcp_f32_e32 v49, v5
	s_nop 0
	v_mul_f32_e32 v49, v50, v49
	v_mul_f32_e32 v1, 0xbfb8aa3b, v6
	v_exp_f32_e32 v1, v1
	s_nop 0
	v_pk_add_f32 v[0:1], v[0:1], 1.0 op_sel_hi:[1,0]
	v_rcp_f32_e32 v48, v4
	s_nop 0
	v_mul_f32_e32 v48, v51, v48
	v_lshlrev_b32_e32 v57, 16, v3
	v_rcp_f32_e32 v51, v1
	s_nop 0
	v_mul_f32_e32 v51, v6, v51
	v_add_co_u32_e64 v4, s[12:13], s80, v82
	s_nop 0
	s_nop 0
	v_addc_co_u32_e64 v5, s[12:13], 0, v83, s[12:13]
	global_load_dwordx4 v[4:7], v[4:5], off offset:512
	v_mul_f32_e32 v50, 0xbfb8aa3b, v58
	v_exp_f32_e32 v52, v50
	v_mul_f32_e32 v50, 0xbfb8aa3b, v57
	v_exp_f32_e32 v53, v50
	v_rcp_f32_e32 v50, v0
	s_nop 0
	v_mul_f32_e32 v50, v54, v50
	v_and_b32_e32 v56, 0xffff0000, v3
	v_pk_add_f32 v[0:1], v[52:53], 1.0 op_sel_hi:[1,0]
	v_and_b32_e32 v59, 0xffff0000, v2
	v_mul_f32_e32 v2, 0xbfb8aa3b, v59
	v_exp_f32_e32 v2, v2
	v_rcp_f32_e32 v53, v1
	s_nop 0
	v_mul_f32_e32 v53, v57, v53
	v_mul_f32_e32 v3, 0xbfb8aa3b, v56
	v_exp_f32_e32 v3, v3
	s_nop 0
	v_pk_add_f32 v[54:55], v[2:3], 1.0 op_sel_hi:[1,0]
	v_rcp_f32_e32 v52, v0
	s_nop 0
	v_mul_f32_e32 v52, v58, v52
	v_rcp_f32_e32 v55, v55
	s_nop 0
	v_mul_f32_e32 v55, v56, v55
	v_add_co_u32_e64 v0, s[12:13], s80, v80
	s_waitcnt vmcnt(0)
	v_lshlrev_b32_e32 v62, 16, v5
	v_lshlrev_b32_e32 v63, 16, v4
	v_mul_f32_e32 v56, 0xbfb8aa3b, v63
	v_mul_f32_e32 v57, 0xbfb8aa3b, v62
	v_exp_f32_e32 v56, v56
	v_exp_f32_e32 v57, v57
	v_addc_co_u32_e64 v1, s[12:13], 0, v81, s[12:13]
	v_rcp_f32_e32 v54, v54
	s_nop 0
	v_mul_f32_e32 v54, v59, v54
	v_pk_add_f32 v[56:57], v[56:57], 1.0 op_sel_hi:[1,0]
	v_and_b32_e32 v58, 0xffff0000, v5
	global_load_dwordx4 v[0:3], v[0:1], off offset:512
	v_and_b32_e32 v64, 0xffff0000, v4
	v_mul_f32_e32 v4, 0xbfb8aa3b, v64
	v_rcp_f32_e32 v57, v57
	s_nop 0
	v_mul_f32_e32 v57, v62, v57
	v_exp_f32_e32 v4, v4
	v_mul_f32_e32 v5, 0xbfb8aa3b, v58
	v_exp_f32_e32 v5, v5
	s_nop 0
	v_pk_add_f32 v[4:5], v[4:5], 1.0 op_sel_hi:[1,0]
	v_rcp_f32_e32 v56, v56
	s_nop 0
	v_mul_f32_e32 v56, v63, v56
	v_lshlrev_b32_e32 v65, 16, v6
	v_rcp_f32_e32 v59, v5
	s_nop 0
	v_mul_f32_e32 v59, v58, v59
	v_lshlrev_b32_e32 v62, 16, v7
	v_mul_f32_e32 v60, 0xbfb8aa3b, v65
	v_mul_f32_e32 v61, 0xbfb8aa3b, v62
	v_exp_f32_e32 v60, v60
	v_exp_f32_e32 v61, v61
	v_rcp_f32_e32 v58, v4
	s_nop 0
	v_mul_f32_e32 v58, v64, v58
	v_and_b32_e32 v63, 0xffff0000, v7
	v_pk_add_f32 v[4:5], v[60:61], 1.0 op_sel_hi:[1,0]
	v_and_b32_e32 v64, 0xffff0000, v6
	v_mul_f32_e32 v6, 0xbfb8aa3b, v64
	v_exp_f32_e32 v6, v6
	v_rcp_f32_e32 v61, v5
	s_nop 0
	v_mul_f32_e32 v61, v62, v61
	v_mul_f32_e32 v7, 0xbfb8aa3b, v63
	v_exp_f32_e32 v7, v7
	s_nop 0
	v_pk_add_f32 v[6:7], v[6:7], 1.0 op_sel_hi:[1,0]
	v_rcp_f32_e32 v60, v4
	s_nop 0
	v_mul_f32_e32 v60, v65, v60
	v_rcp_f32_e32 v4, v7
	s_nop 0
	v_mul_f32_e32 v63, v63, v4
	s_waitcnt vmcnt(0)
	v_lshlrev_b32_e32 v66, 16, v1
	v_lshlrev_b32_e32 v67, 16, v0
	v_mul_f32_e32 v4, 0xbfb8aa3b, v67
	v_mul_f32_e32 v5, 0xbfb8aa3b, v66
	v_exp_f32_e32 v4, v4
	v_exp_f32_e32 v5, v5
	v_and_b32_e32 v68, 0xffff0000, v1
	v_rcp_f32_e32 v62, v6
	s_nop 0
	v_mul_f32_e32 v62, v64, v62
	v_pk_add_f32 v[4:5], v[4:5], 1.0 op_sel_hi:[1,0]
	v_and_b32_e32 v69, 0xffff0000, v0
	v_mul_f32_e32 v0, 0xbfb8aa3b, v69
	v_exp_f32_e32 v6, v0
	v_and_b32_e32 v80, 0xffff0000, v2
	v_rcp_f32_e32 v1, v5
	s_nop 0
	v_mul_f32_e32 v1, v66, v1
	v_mul_f32_e32 v7, 0xbfb8aa3b, v68
	v_exp_f32_e32 v7, v7
	s_nop 0
	v_pk_add_f32 v[64:65], v[6:7], 1.0 op_sel_hi:[1,0]
	v_rcp_f32_e32 v0, v4
	s_nop 0
	v_mul_f32_e32 v0, v67, v0
	v_rcp_f32_e32 v65, v65
	s_nop 0
	v_mul_f32_e32 v65, v68, v65
	v_add_co_u32_e64 v4, s[12:13], s80, v78
	s_nop 0
	s_nop 0
	v_addc_co_u32_e64 v5, s[12:13], 0, v79, s[12:13]
	global_load_dwordx4 v[4:7], v[4:5], off offset:512
	v_lshlrev_b32_e32 v78, 16, v3
	v_lshlrev_b32_e32 v79, 16, v2
	v_mul_f32_e32 v66, 0xbfb8aa3b, v79
	v_mul_f32_e32 v67, 0xbfb8aa3b, v78
	v_exp_f32_e32 v66, v66
	v_exp_f32_e32 v67, v67
	v_and_b32_e32 v70, 0xffff0000, v3
	v_rcp_f32_e32 v64, v64
	s_nop 0
	v_mul_f32_e32 v64, v69, v64
	v_pk_add_f32 v[66:67], v[66:67], 1.0 op_sel_hi:[1,0]
	v_mul_f32_e32 v2, 0xbfb8aa3b, v80
	v_exp_f32_e32 v68, v2
	v_mul_f32_e32 v69, 0xbfb8aa3b, v70
	v_exp_f32_e32 v69, v69
	v_rcp_f32_e32 v3, v67
	s_nop 0
	v_mul_f32_e32 v3, v78, v3
	v_pk_add_f32 v[68:69], v[68:69], 1.0 op_sel_hi:[1,0]
	v_rcp_f32_e32 v2, v66
	s_nop 0
	v_mul_f32_e32 v2, v79, v2
	v_rcp_f32_e32 v67, v69
	s_nop 0
	v_mul_f32_e32 v67, v70, v67
	v_add_co_u32_e64 v70, s[12:13], s80, v76
	s_nop 0
	s_nop 0
	v_addc_co_u32_e64 v71, s[12:13], 0, v77, s[12:13]
	global_load_dwordx4 v[76:79], v[70:71], off offset:512
	v_rcp_f32_e32 v66, v68
	s_nop 0
	v_mul_f32_e32 v66, v80, v66
	s_waitcnt vmcnt(1)
	v_lshlrev_b32_e32 v82, 16, v5
	v_lshlrev_b32_e32 v83, 16, v4
	v_mul_f32_e32 v70, 0xbfb8aa3b, v83
	v_mul_f32_e32 v71, 0xbfb8aa3b, v82
	v_exp_f32_e32 v70, v70
	v_exp_f32_e32 v71, v71
	v_and_b32_e32 v80, 0xffff0000, v5
	v_and_b32_e32 v84, 0xffff0000, v4
	v_mul_f32_e32 v4, 0xbfb8aa3b, v84
	v_pk_add_f32 v[68:69], v[70:71], 1.0 op_sel_hi:[1,0]
	v_exp_f32_e32 v70, v4
	s_waitcnt lgkmcnt(0)
	s_barrier
; __device__ __forceinline__ unsigned pack2(float a, float b) { return (unsigned)f2bf(a) | ((unsigned)f2bf(b) << 16); }
; __device__ __forceinline__ float bflo(unsigned w) { return __uint_as_float(w << 16); }
; __device__ __forceinline__ float bfhi(unsigned w) { return __uint_as_float(w & 0xffff0000u); }
; __device__ __forceinline__ float silu_f(float g) { return g / (1.f + __expf(-g)); }
; template <int DH, int MODE>
; __device__ void attn_item(const Params& p, int layer, int b, int blk, int head, char* smem) {
;     ...
;     for (int i = 0; i < NCH; ++i) {
;       int q = tid + 256 * i, r = q / CPR, c = (q % CPR) * 8;
;       float4 m0 = *reinterpret_cast<const float4*>(Of + r * OST + c);
;       float4 m1 = *reinterpret_cast<const float4*>(Of + r * OST + c + 4);
;       float mm[8] = {m0.x, m0.y, m0.z, m0.w, m1.x, m1.y, m1.z, m1.w};
;       unsigned gw[4] = {gt[i].x, gt[i].y, gt[i].z, gt[i].w};
;       unsigned ow[4];
; #pragma unroll
;       for (int e = 0; e < 4; ++e)
;         ow[e] = pack2(mm[2 * e] * silu_f(bflo(gw[e])), mm[2 * e + 1] * silu_f(bfhi(gw[e])));
;       *reinterpret_cast<uint4*>(Y + (tq0 + r) * YW + ycol + c) = make_uint4(ow[0], ow[1], ow[2], ow[3]);
	v_mul_f32_e32 v71, 0xbfb8aa3b, v80
	v_exp_f32_e32 v71, v71
	v_rcp_f32_e32 v5, v69
	s_nop 0
	v_mul_f32_e32 v5, v82, v5
	v_pk_add_f32 v[70:71], v[70:71], 1.0 op_sel_hi:[1,0]
	v_rcp_f32_e32 v4, v68
	s_nop 0
	v_mul_f32_e32 v4, v83, v4
	v_rcp_f32_e32 v69, v71
	s_nop 0
	v_mul_f32_e32 v69, v80, v69
	v_lshlrev_b32_e32 v82, 16, v7
	v_lshlrev_b32_e32 v85, 16, v6
	v_mul_f32_e32 v80, 0xbfb8aa3b, v85
	v_mul_f32_e32 v81, 0xbfb8aa3b, v82
	v_exp_f32_e32 v80, v80
	v_exp_f32_e32 v81, v81
	v_rcp_f32_e32 v68, v70
	s_nop 0
	v_mul_f32_e32 v68, v84, v68
	v_and_b32_e32 v83, 0xffff0000, v7
	v_pk_add_f32 v[70:71], v[80:81], 1.0 op_sel_hi:[1,0]
	v_and_b32_e32 v84, 0xffff0000, v6
	v_mul_f32_e32 v6, 0xbfb8aa3b, v84
	v_exp_f32_e32 v80, v6
	s_waitcnt vmcnt(0)
	v_and_b32_e32 v94, 0xffff0000, v78
	v_mul_f32_e32 v81, 0xbfb8aa3b, v83
	v_exp_f32_e32 v81, v81
	v_rcp_f32_e32 v7, v71
	s_nop 0
	v_mul_f32_e32 v7, v82, v7
	v_pk_add_f32 v[80:81], v[80:81], 1.0 op_sel_hi:[1,0]
	v_rcp_f32_e32 v6, v70
	s_nop 0
	v_mul_f32_e32 v6, v85, v6
	v_rcp_f32_e32 v71, v81
	s_nop 0
	v_mul_f32_e32 v71, v83, v71
	v_lshlrev_b32_e32 v86, 16, v77
	v_lshlrev_b32_e32 v87, 16, v76
	v_mul_f32_e32 v82, 0xbfb8aa3b, v87
	v_mul_f32_e32 v83, 0xbfb8aa3b, v86
	v_exp_f32_e32 v82, v82
	v_exp_f32_e32 v83, v83
	v_rcp_f32_e32 v70, v80
	s_nop 0
	v_mul_f32_e32 v70, v84, v70
	v_and_b32_e32 v88, 0xffff0000, v77
	v_pk_add_f32 v[80:81], v[82:83], 1.0 op_sel_hi:[1,0]
	v_and_b32_e32 v83, 0xffff0000, v76
	v_mul_f32_e32 v76, 0xbfb8aa3b, v83
	v_exp_f32_e32 v76, v76
	v_rcp_f32_e32 v85, v81
	s_nop 0
	v_mul_f32_e32 v85, v86, v85
	v_mul_f32_e32 v77, 0xbfb8aa3b, v88
	v_exp_f32_e32 v77, v77
	s_nop 0
	v_pk_add_f32 v[76:77], v[76:77], 1.0 op_sel_hi:[1,0]
	v_rcp_f32_e32 v84, v80
	s_nop 0
	v_mul_f32_e32 v84, v87, v84
	v_rcp_f32_e32 v87, v77
	s_nop 0
	v_mul_f32_e32 v87, v88, v87
	v_lshlrev_b32_e32 v90, 16, v78
	v_lshlrev_b32_e32 v82, 16, v79
	v_mul_f32_e32 v80, 0xbfb8aa3b, v90
	v_mul_f32_e32 v81, 0xbfb8aa3b, v82
	v_exp_f32_e32 v80, v80
	v_exp_f32_e32 v81, v81
	v_rcp_f32_e32 v86, v76
	s_nop 0
	v_mul_f32_e32 v86, v83, v86
	v_and_b32_e32 v83, 0xffff0000, v79
	v_pk_add_f32 v[76:77], v[80:81], 1.0 op_sel_hi:[1,0]
	v_mul_f32_e32 v78, 0xbfb8aa3b, v94
	v_exp_f32_e32 v78, v78
	v_rcp_f32_e32 v89, v77
	s_nop 0
	v_mul_f32_e32 v89, v82, v89
	v_mul_f32_e32 v79, 0xbfb8aa3b, v83
	v_exp_f32_e32 v79, v79
	s_nop 0
	v_pk_add_f32 v[80:81], v[78:79], 1.0 op_sel_hi:[1,0]
	v_rcp_f32_e32 v88, v76
	s_nop 0
	v_mul_f32_e32 v88, v90, v88
	v_rcp_f32_e32 v91, v81
	s_nop 0
	v_mul_f32_e32 v91, v83, v91
	ds_read_b128 v[76:79], v98
	v_rcp_f32_e32 v90, v80
	s_nop 0
	v_mul_f32_e32 v90, v94, v90
	ds_read_b128 v[80:83], v98 offset:16
	v_add_co_u32_e32 v30, vcc, s77, v30
	s_waitcnt lgkmcnt(1)
	v_mov_b32_e32 v96, v76
	v_mov_b32_e32 v97, v78
	v_pk_mul_f32 v[84:85], v[84:85], v[96:97]
	v_mov_b32_e32 v78, v77
	v_pk_mul_f32 v[76:77], v[86:87], v[78:79]
	v_cvt_pk_bf16_f32 v79, 0, v84
	v_cvt_pk_bf16_f32 v78, 0, v85
	v_cvt_pk_bf16_f32 v77, 0, v77
	v_cvt_pk_bf16_f32 v76, 0, v76
	v_and_b32_e32 v77, 0xffff0000, v77
	v_and_b32_e32 v76, 0xffff0000, v76
	v_or_b32_sdwa v77, v77, v78 dst_sel:DWORD dst_unused:UNUSED_PAD src0_sel:DWORD src1_sel:WORD_1
	v_or_b32_sdwa v76, v76, v79 dst_sel:DWORD dst_unused:UNUSED_PAD src0_sel:DWORD src1_sel:WORD_1
	s_waitcnt lgkmcnt(0)
	v_mov_b32_e32 v78, v80
	v_mov_b32_e32 v79, v82
	v_pk_mul_f32 v[78:79], v[88:89], v[78:79]
	v_mov_b32_e32 v82, v81
	v_pk_mul_f32 v[80:81], v[90:91], v[82:83]
	v_cvt_pk_bf16_f32 v78, 0, v78
	v_cvt_pk_bf16_f32 v79, 0, v79
	v_cvt_pk_bf16_f32 v81, 0, v81
	v_cvt_pk_bf16_f32 v80, 0, v80
	v_and_b32_e32 v81, 0xffff0000, v81
	v_and_b32_e32 v80, 0xffff0000, v80
	v_or_b32_sdwa v79, v81, v79 dst_sel:DWORD dst_unused:UNUSED_PAD src0_sel:DWORD src1_sel:WORD_1
	v_or_b32_sdwa v78, v80, v78 dst_sel:DWORD dst_unused:UNUSED_PAD src0_sel:DWORD src1_sel:WORD_1
	ds_read_b128 v[80:83], v95
	v_addc_co_u32_e32 v31, vcc, 0, v31, vcc
	global_store_dwordx4 v[30:31], v[76:79], off offset:2048
	s_nop 0
	ds_read_b128 v[76:79], v95 offset:16
	s_waitcnt lgkmcnt(1)
	v_mov_b32_e32 v30, v80
	v_mov_b32_e32 v31, v82
	v_pk_mul_f32 v[4:5], v[4:5], v[30:31]
	v_mov_b32_e32 v82, v81
	v_pk_mul_f32 v[30:31], v[68:69], v[82:83]
	v_cvt_pk_bf16_f32 v4, 0, v4
	v_cvt_pk_bf16_f32 v5, 0, v5
	v_cvt_pk_bf16_f32 v31, 0, v31
	v_cvt_pk_bf16_f32 v30, 0, v30
	v_and_b32_e32 v31, 0xffff0000, v31
	v_and_b32_e32 v30, 0xffff0000, v30
	v_or_b32_sdwa v5, v31, v5 dst_sel:DWORD dst_unused:UNUSED_PAD src0_sel:DWORD src1_sel:WORD_1
	v_or_b32_sdwa v4, v30, v4 dst_sel:DWORD dst_unused:UNUSED_PAD src0_sel:DWORD src1_sel:WORD_1
	s_waitcnt lgkmcnt(0)
	v_mov_b32_e32 v30, v76
	v_mov_b32_e32 v31, v78
	v_pk_mul_f32 v[6:7], v[6:7], v[30:31]
	v_mov_b32_e32 v78, v77
	v_pk_mul_f32 v[30:31], v[70:71], v[78:79]
	v_cvt_pk_bf16_f32 v6, 0, v6
	v_cvt_pk_bf16_f32 v7, 0, v7
	v_cvt_pk_bf16_f32 v31, 0, v31
	v_cvt_pk_bf16_f32 v30, 0, v30
	ds_read_b128 v[68:71], v93
	v_and_b32_e32 v31, 0xffff0000, v31
	v_and_b32_e32 v30, 0xffff0000, v30
	v_add_co_u32_e32 v26, vcc, s77, v26
	v_or_b32_sdwa v7, v31, v7 dst_sel:DWORD dst_unused:UNUSED_PAD src0_sel:DWORD src1_sel:WORD_1
	v_or_b32_sdwa v6, v30, v6 dst_sel:DWORD dst_unused:UNUSED_PAD src0_sel:DWORD src1_sel:WORD_1
	v_addc_co_u32_e32 v27, vcc, 0, v27, vcc
	global_store_dwordx4 v[26:27], v[4:7], off offset:2048
	s_waitcnt lgkmcnt(0)
	v_mov_b32_e32 v26, v68
	v_mov_b32_e32 v27, v70
	ds_read_b128 v[4:7], v93 offset:16
	v_pk_mul_f32 v[0:1], v[0:1], v[26:27]
	v_mov_b32_e32 v70, v69
	v_pk_mul_f32 v[26:27], v[64:65], v[70:71]
	v_cvt_pk_bf16_f32 v0, 0, v0
	v_cvt_pk_bf16_f32 v1, 0, v1
	v_cvt_pk_bf16_f32 v27, 0, v27
	v_cvt_pk_bf16_f32 v26, 0, v26
	v_and_b32_e32 v27, 0xffff0000, v27
	v_and_b32_e32 v26, 0xffff0000, v26
	v_or_b32_sdwa v1, v27, v1 dst_sel:DWORD dst_unused:UNUSED_PAD src0_sel:DWORD src1_sel:WORD_1
	v_or_b32_sdwa v0, v26, v0 dst_sel:DWORD dst_unused:UNUSED_PAD src0_sel:DWORD src1_sel:WORD_1
	s_waitcnt lgkmcnt(0)
; __device__ __forceinline__ unsigned pack2(float a, float b) { return (unsigned)f2bf(a) | ((unsigned)f2bf(b) << 16); }
; __device__ __forceinline__ float bflo(unsigned w) { return __uint_as_float(w << 16); }
; __device__ __forceinline__ float bfhi(unsigned w) { return __uint_as_float(w & 0xffff0000u); }
; __device__ __forceinline__ float silu_f(float g) { return g / (1.f + __expf(-g)); }
; template <int DH, int MODE>
; __device__ void attn_item(const Params& p, int layer, int b, int blk, int head, char* smem) {
;     ...
;     for (int i = 0; i < NCH; ++i) {
;       int q = tid + 256 * i, r = q / CPR, c = (q % CPR) * 8;
;       float4 m0 = *reinterpret_cast<const float4*>(Of + r * OST + c);
;       float4 m1 = *reinterpret_cast<const float4*>(Of + r * OST + c + 4);
;       float mm[8] = {m0.x, m0.y, m0.z, m0.w, m1.x, m1.y, m1.z, m1.w};
;       unsigned gw[4] = {gt[i].x, gt[i].y, gt[i].z, gt[i].w};
;       unsigned ow[4];
; #pragma unroll
;       for (int e = 0; e < 4; ++e)
;         ow[e] = pack2(mm[2 * e] * silu_f(bflo(gw[e])), mm[2 * e + 1] * silu_f(bfhi(gw[e])));
;       *reinterpret_cast<uint4*>(Y + (tq0 + r) * YW + ycol + c) = make_uint4(ow[0], ow[1], ow[2], ow[3]);
	v_mov_b32_e32 v26, v4
	v_mov_b32_e32 v27, v6
	v_pk_mul_f32 v[2:3], v[2:3], v[26:27]
	v_mov_b32_e32 v6, v5
	v_pk_mul_f32 v[4:5], v[66:67], v[6:7]
	v_cvt_pk_bf16_f32 v2, 0, v2
	v_cvt_pk_bf16_f32 v3, 0, v3
	v_cvt_pk_bf16_f32 v5, 0, v5
	v_cvt_pk_bf16_f32 v4, 0, v4
	v_and_b32_e32 v5, 0xffff0000, v5
	v_and_b32_e32 v4, 0xffff0000, v4
	v_or_b32_sdwa v3, v5, v3 dst_sel:DWORD dst_unused:UNUSED_PAD src0_sel:DWORD src1_sel:WORD_1
	v_or_b32_sdwa v2, v4, v2 dst_sel:DWORD dst_unused:UNUSED_PAD src0_sel:DWORD src1_sel:WORD_1
	ds_read_b128 v[4:7], v92
	v_add_co_u32_e32 v20, vcc, s77, v20
	s_nop 1
	v_addc_co_u32_e32 v21, vcc, 0, v21, vcc
	global_store_dwordx4 v[20:21], v[0:3], off offset:2048
	s_waitcnt lgkmcnt(0)
	v_mov_b32_e32 v20, v4
	v_mov_b32_e32 v21, v6
	ds_read_b128 v[0:3], v92 offset:16
	v_pk_mul_f32 v[20:21], v[56:57], v[20:21]
	v_mov_b32_e32 v6, v5
	v_pk_mul_f32 v[4:5], v[58:59], v[6:7]
	v_cvt_pk_bf16_f32 v7, 0, v20
	v_cvt_pk_bf16_f32 v6, 0, v21
	v_cvt_pk_bf16_f32 v5, 0, v5
	v_cvt_pk_bf16_f32 v4, 0, v4
	v_and_b32_e32 v5, 0xffff0000, v5
	v_and_b32_e32 v4, 0xffff0000, v4
	v_or_b32_sdwa v5, v5, v6 dst_sel:DWORD dst_unused:UNUSED_PAD src0_sel:DWORD src1_sel:WORD_1
	v_or_b32_sdwa v4, v4, v7 dst_sel:DWORD dst_unused:UNUSED_PAD src0_sel:DWORD src1_sel:WORD_1
	s_waitcnt lgkmcnt(0)
	v_mov_b32_e32 v6, v0
	v_mov_b32_e32 v7, v2
	v_pk_mul_f32 v[6:7], v[60:61], v[6:7]
	v_mov_b32_e32 v2, v1
	v_pk_mul_f32 v[0:1], v[62:63], v[2:3]
	v_cvt_pk_bf16_f32 v3, 0, v6
	v_cvt_pk_bf16_f32 v2, 0, v7
	v_cvt_pk_bf16_f32 v1, 0, v1
	v_cvt_pk_bf16_f32 v0, 0, v0
	v_and_b32_e32 v1, 0xffff0000, v1
	v_and_b32_e32 v0, 0xffff0000, v0
	v_or_b32_sdwa v7, v1, v2 dst_sel:DWORD dst_unused:UNUSED_PAD src0_sel:DWORD src1_sel:WORD_1
	v_or_b32_sdwa v6, v0, v3 dst_sel:DWORD dst_unused:UNUSED_PAD src0_sel:DWORD src1_sel:WORD_1
	ds_read_b128 v[0:3], v75
	v_add_co_u32_e32 v16, vcc, s77, v16
	s_nop 1
	v_addc_co_u32_e32 v17, vcc, 0, v17, vcc
	global_store_dwordx4 v[16:17], v[4:7], off offset:2048
	s_waitcnt lgkmcnt(0)
	v_mov_b32_e32 v16, v0
	v_mov_b32_e32 v17, v2
	ds_read_b128 v[4:7], v75 offset:16
	v_pk_mul_f32 v[16:17], v[48:49], v[16:17]
	v_mov_b32_e32 v2, v1
	v_pk_mul_f32 v[0:1], v[50:51], v[2:3]
	v_cvt_pk_bf16_f32 v3, 0, v16
	v_cvt_pk_bf16_f32 v2, 0, v17
	v_cvt_pk_bf16_f32 v1, 0, v1
	v_cvt_pk_bf16_f32 v0, 0, v0
	v_and_b32_e32 v1, 0xffff0000, v1
	v_and_b32_e32 v0, 0xffff0000, v0
	v_or_b32_sdwa v1, v1, v2 dst_sel:DWORD dst_unused:UNUSED_PAD src0_sel:DWORD src1_sel:WORD_1
	v_or_b32_sdwa v0, v0, v3 dst_sel:DWORD dst_unused:UNUSED_PAD src0_sel:DWORD src1_sel:WORD_1
	s_waitcnt lgkmcnt(0)
	v_mov_b32_e32 v2, v4
	v_mov_b32_e32 v3, v6
	v_pk_mul_f32 v[2:3], v[52:53], v[2:3]
	v_mov_b32_e32 v6, v5
	v_pk_mul_f32 v[4:5], v[54:55], v[6:7]
	v_cvt_pk_bf16_f32 v2, 0, v2
	v_cvt_pk_bf16_f32 v3, 0, v3
	v_cvt_pk_bf16_f32 v5, 0, v5
	v_cvt_pk_bf16_f32 v4, 0, v4
	v_and_b32_e32 v5, 0xffff0000, v5
	v_and_b32_e32 v4, 0xffff0000, v4
	v_or_b32_sdwa v3, v5, v3 dst_sel:DWORD dst_unused:UNUSED_PAD src0_sel:DWORD src1_sel:WORD_1
	v_or_b32_sdwa v2, v4, v2 dst_sel:DWORD dst_unused:UNUSED_PAD src0_sel:DWORD src1_sel:WORD_1
	ds_read_b128 v[4:7], v74
	v_add_co_u32_e32 v12, vcc, s77, v12
	s_nop 1
	v_addc_co_u32_e32 v13, vcc, 0, v13, vcc
	global_store_dwordx4 v[12:13], v[0:3], off offset:2048
	s_waitcnt lgkmcnt(0)
; __device__ __forceinline__ unsigned pack2(float a, float b) { return (unsigned)f2bf(a) | ((unsigned)f2bf(b) << 16); }
; __device__ __forceinline__ float bflo(unsigned w) { return __uint_as_float(w << 16); }
; __device__ __forceinline__ float bfhi(unsigned w) { return __uint_as_float(w & 0xffff0000u); }
; __device__ __forceinline__ float silu_f(float g) { return g / (1.f + __expf(-g)); }
; template <int DH, int MODE>
; __device__ void attn_item(const Params& p, int layer, int b, int blk, int head, char* smem) {
;     ...
;     for (int i = 0; i < NCH; ++i) {
;       int q = tid + 256 * i, r = q / CPR, c = (q % CPR) * 8;
;       float4 m0 = *reinterpret_cast<const float4*>(Of + r * OST + c);
;       float4 m1 = *reinterpret_cast<const float4*>(Of + r * OST + c + 4);
;       float mm[8] = {m0.x, m0.y, m0.z, m0.w, m1.x, m1.y, m1.z, m1.w};
;       unsigned gw[4] = {gt[i].x, gt[i].y, gt[i].z, gt[i].w};
;       unsigned ow[4];
; #pragma unroll
;       for (int e = 0; e < 4; ++e)
;         ow[e] = pack2(mm[2 * e] * silu_f(bflo(gw[e])), mm[2 * e + 1] * silu_f(bfhi(gw[e])));
;       *reinterpret_cast<uint4*>(Y + (tq0 + r) * YW + ycol + c) = make_uint4(ow[0], ow[1], ow[2], ow[3]);
;     }
;   }
;   __syncthreads();
	v_mov_b32_e32 v12, v4
	v_mov_b32_e32 v13, v6
	ds_read_b128 v[0:3], v74 offset:16
	v_pk_mul_f32 v[12:13], v[40:41], v[12:13]
	v_mov_b32_e32 v6, v5
	v_pk_mul_f32 v[4:5], v[42:43], v[6:7]
	v_cvt_pk_bf16_f32 v7, 0, v12
	v_cvt_pk_bf16_f32 v6, 0, v13
	v_cvt_pk_bf16_f32 v5, 0, v5
	v_cvt_pk_bf16_f32 v4, 0, v4
	v_and_b32_e32 v5, 0xffff0000, v5
	v_and_b32_e32 v4, 0xffff0000, v4
	v_or_b32_sdwa v5, v5, v6 dst_sel:DWORD dst_unused:UNUSED_PAD src0_sel:DWORD src1_sel:WORD_1
	v_or_b32_sdwa v4, v4, v7 dst_sel:DWORD dst_unused:UNUSED_PAD src0_sel:DWORD src1_sel:WORD_1
	s_waitcnt lgkmcnt(0)
	v_mov_b32_e32 v6, v0
	v_mov_b32_e32 v7, v2
	v_pk_mul_f32 v[6:7], v[44:45], v[6:7]
	v_mov_b32_e32 v2, v1
	v_pk_mul_f32 v[0:1], v[46:47], v[2:3]
	v_cvt_pk_bf16_f32 v3, 0, v6
	v_cvt_pk_bf16_f32 v2, 0, v7
	v_cvt_pk_bf16_f32 v1, 0, v1
	v_cvt_pk_bf16_f32 v0, 0, v0
	v_and_b32_e32 v1, 0xffff0000, v1
	v_and_b32_e32 v0, 0xffff0000, v0
	v_or_b32_sdwa v7, v1, v2 dst_sel:DWORD dst_unused:UNUSED_PAD src0_sel:DWORD src1_sel:WORD_1
	v_or_b32_sdwa v6, v0, v3 dst_sel:DWORD dst_unused:UNUSED_PAD src0_sel:DWORD src1_sel:WORD_1
	ds_read_b128 v[0:3], v73
	v_add_co_u32_e32 v10, vcc, s77, v10
	s_nop 1
	v_addc_co_u32_e32 v11, vcc, 0, v11, vcc
	global_store_dwordx4 v[10:11], v[4:7], off offset:2048
	s_waitcnt lgkmcnt(0)
	v_mov_b32_e32 v10, v0
	v_mov_b32_e32 v11, v2
	ds_read_b128 v[4:7], v73 offset:16
	v_pk_mul_f32 v[10:11], v[32:33], v[10:11]
	v_mov_b32_e32 v2, v1
	v_pk_mul_f32 v[0:1], v[34:35], v[2:3]
	v_cvt_pk_bf16_f32 v3, 0, v10
	v_cvt_pk_bf16_f32 v2, 0, v11
	v_cvt_pk_bf16_f32 v1, 0, v1
	v_cvt_pk_bf16_f32 v0, 0, v0
	v_and_b32_e32 v1, 0xffff0000, v1
	v_and_b32_e32 v0, 0xffff0000, v0
	v_or_b32_sdwa v1, v1, v2 dst_sel:DWORD dst_unused:UNUSED_PAD src0_sel:DWORD src1_sel:WORD_1
	v_or_b32_sdwa v0, v0, v3 dst_sel:DWORD dst_unused:UNUSED_PAD src0_sel:DWORD src1_sel:WORD_1
	s_waitcnt lgkmcnt(0)
	v_mov_b32_e32 v2, v4
	v_mov_b32_e32 v3, v6
	v_pk_mul_f32 v[2:3], v[36:37], v[2:3]
	v_mov_b32_e32 v6, v5
	v_pk_mul_f32 v[4:5], v[38:39], v[6:7]
	v_cvt_pk_bf16_f32 v2, 0, v2
	v_cvt_pk_bf16_f32 v3, 0, v3
	v_cvt_pk_bf16_f32 v5, 0, v5
	v_cvt_pk_bf16_f32 v4, 0, v4
	v_and_b32_e32 v5, 0xffff0000, v5
	v_and_b32_e32 v4, 0xffff0000, v4
	v_or_b32_sdwa v3, v5, v3 dst_sel:DWORD dst_unused:UNUSED_PAD src0_sel:DWORD src1_sel:WORD_1
	v_or_b32_sdwa v2, v4, v2 dst_sel:DWORD dst_unused:UNUSED_PAD src0_sel:DWORD src1_sel:WORD_1
	ds_read_b128 v[4:7], v72
	v_add_co_u32_e32 v8, vcc, s77, v8
	s_nop 1
	v_addc_co_u32_e32 v9, vcc, 0, v9, vcc
	global_store_dwordx4 v[8:9], v[0:3], off offset:2048
	s_waitcnt lgkmcnt(0)
	v_mov_b32_e32 v8, v4
	v_mov_b32_e32 v9, v6
	ds_read_b128 v[0:3], v72 offset:16
	v_pk_mul_f32 v[8:9], v[18:19], v[8:9]
	v_mov_b32_e32 v6, v5
	v_pk_mul_f32 v[4:5], v[22:23], v[6:7]
	v_cvt_pk_bf16_f32 v7, 0, v8
	v_cvt_pk_bf16_f32 v6, 0, v9
	v_cvt_pk_bf16_f32 v5, 0, v5
	v_cvt_pk_bf16_f32 v4, 0, v4
	v_and_b32_e32 v5, 0xffff0000, v5
	v_and_b32_e32 v4, 0xffff0000, v4
	v_or_b32_sdwa v5, v5, v6 dst_sel:DWORD dst_unused:UNUSED_PAD src0_sel:DWORD src1_sel:WORD_1
	v_or_b32_sdwa v4, v4, v7 dst_sel:DWORD dst_unused:UNUSED_PAD src0_sel:DWORD src1_sel:WORD_1
	s_waitcnt lgkmcnt(0)
	v_mov_b32_e32 v6, v0
	v_mov_b32_e32 v7, v2
	v_pk_mul_f32 v[6:7], v[24:25], v[6:7]
	v_mov_b32_e32 v2, v1
	v_pk_mul_f32 v[0:1], v[28:29], v[2:3]
	v_cvt_pk_bf16_f32 v2, 0, v7
	v_cvt_pk_bf16_f32 v3, 0, v6
	v_cvt_pk_bf16_f32 v0, 0, v0
	v_cvt_pk_bf16_f32 v1, 0, v1
	v_and_b32_e32 v0, 0xffff0000, v0
	v_and_b32_e32 v1, 0xffff0000, v1
	v_or_b32_sdwa v6, v0, v3 dst_sel:DWORD dst_unused:UNUSED_PAD src0_sel:DWORD src1_sel:WORD_1
	v_add_co_u32_e32 v0, vcc, 0x184a1000, v14
	v_or_b32_sdwa v7, v1, v2 dst_sel:DWORD dst_unused:UNUSED_PAD src0_sel:DWORD src1_sel:WORD_1
	s_nop 0
	v_addc_co_u32_e32 v1, vcc, 0, v15, vcc
	global_store_dwordx4 v[0:1], v[4:7], off offset:2048
	s_barrier

; __device__ __forceinline__ float bflo(unsigned w) { return __uint_as_float(w << 16); }
; __device__ __forceinline__ float bfhi(unsigned w) { return __uint_as_float(w & 0xffff0000u); }
; __device__ void gmlp_item(const Params& p, int layer, int b, int n, int g, char* smem) {
;     ...
;   {
;     uint4 raw[8];
; #pragma unroll
;     for (int i = 0; i < 8; ++i) {
;       int q = tid + 256 * i;
;       int st = q & 127, c0 = (q >> 7) * 8;
;       raw[i] = *reinterpret_cast<const uint4*>(P + (t0 + st) * NP + 512 + g * 128 + c0);
;     }
; #pragma unroll
;     for (int i = 0; i < 8; ++i) {
;       int q = tid + 256 * i;
;       int st = q & 127, c0 = (q >> 7) * 8;
;       unsigned w[4] = {raw[i].x, raw[i].y, raw[i].z, raw[i].w};
;       float mu = mu_s[st], rs = rs_s[st];
;       const float4* gp = reinterpret_cast<const float4*>(p.gm_gain + (size_t)layer * 512 + g * 128 + c0);
;       float4 g0 = gp[0], g1 = gp[1];
;       float gg[8] = {g0.x, g0.y, g0.z, g0.w, g1.x, g1.y, g1.z, g1.w};
; #pragma unroll
;       for (int e = 0; e < 8; ++e) {
;         float v = (e & 1) ? bfhi(w[e >> 1]) : bflo(w[e >> 1]);
;         float val = (v - mu) * rs * gg[e];
;         *reinterpret_cast<u16*>(smem + 32768 + (st >> 5) * 8192 + (c0 + e) * 64 + (st & 31) * 2) = f2bf(val);
;       }
.LBB0_800:
	s_or_b64 exec, exec, s[14:15]
	v_and_b32_e32 v6, 0x7f, v59
	s_ashr_i32 s14, s16, 31
	s_bfe_u32 s20, s82, 0x20003
	s_waitcnt lgkmcnt(0)
	v_or_b32_e32 v0, s36, v6
	s_add_u32 s21, s28, s16
	v_mul_lo_u32 v128, v0, s66
	v_ashrrev_i32_e32 v48, 4, v59
	s_addc_u32 s48, s29, s14
	v_lshl_add_u64 v[0:1], v[128:129], 1, s[12:13]
	s_lshl_b32 s14, s20, 8
	s_mov_b32 s15, s37
	v_and_b32_e32 v2, -8, v48
	v_lshl_add_u64 v[0:1], v[0:1], 0, s[14:15]
	v_ashrrev_i32_e32 v3, 31, v2
	v_lshl_add_u64 v[4:5], v[2:3], 1, v[0:1]
	s_barrier
	global_load_dwordx4 v[28:31], v[4:5], off offset:1024
	s_lshl_b32 s16, s20, 7
	s_lshl_b32 s14, s20, 9
	s_add_u32 s14, s55, s14
	s_addc_u32 s15, s27, 0
	v_lshl_add_u64 v[4:5], v[2:3], 2, s[14:15]
	global_load_dwordx4 v[50:53], v[4:5], off
	global_load_dwordx4 v[70:73], v[4:5], off offset:16
	v_add_u32_e32 v3, 0x100, v59
	v_ashrrev_i32_e32 v68, 4, v3
	v_add_u32_e32 v4, 0x200, v59
	v_lshlrev_b32_e32 v12, 1, v59
	v_and_b32_e32 v54, -8, v68
	v_add_u32_e32 v5, 0x300, v59
	v_lshlrev_b32_e32 v11, 8, v59
	v_ashrrev_i32_e32 v66, 4, v4
	v_and_b32_e32 v4, 62, v12
	v_ashrrev_i32_e32 v55, 31, v54
	v_ashrrev_i32_e32 v64, 4, v5
	v_and_or_b32 v44, v11, s67, v4
	v_lshl_add_u64 v[4:5], v[54:55], 1, v[0:1]
	global_load_dwordx4 v[24:27], v[4:5], off offset:1024
	v_lshl_add_u64 v[4:5], v[54:55], 2, s[14:15]
	global_load_dwordx4 v[74:77], v[4:5], off offset:16
	global_load_dwordx4 v[78:81], v[4:5], off
	v_lshlrev_b32_e32 v3, 2, v6
	v_or_b32_e32 v6, 0x10000, v3
	v_or_b32_e32 v3, 0x10200, v3
	ds_read_b32 v45, v6
	ds_read_b32 v46, v3
	v_add_u32_e32 v7, 0x400, v59
	v_add_u32_e32 v8, 0x500, v59
	v_add_u32_e32 v9, 0x600, v59
	v_add_u32_e32 v10, 0x700, v59
	v_ashrrev_i32_e32 v62, 4, v7
	v_ashrrev_i32_e32 v60, 4, v8
	v_ashrrev_i32_e32 v58, 4, v9
	v_ashrrev_i32_e32 v56, 4, v10
	v_and_b32_e32 v42, -8, v66
	v_and_b32_e32 v40, -8, v64
	v_and_b32_e32 v38, -8, v62
	v_and_b32_e32 v36, -8, v60
	v_and_b32_e32 v34, -8, v58
	v_and_b32_e32 v32, -8, v56
	v_ashrrev_i32_e32 v43, 31, v42
	v_ashrrev_i32_e32 v41, 31, v40
	v_ashrrev_i32_e32 v39, 31, v38
	v_ashrrev_i32_e32 v37, 31, v36
	v_ashrrev_i32_e32 v35, 31, v34
	v_ashrrev_i32_e32 v33, 31, v32
	v_lshl_add_u32 v47, v2, 6, v44
	v_lshl_add_u64 v[2:3], v[42:43], 1, v[0:1]
	v_lshl_add_u64 v[4:5], v[40:41], 1, v[0:1]
	v_lshl_add_u64 v[6:7], v[38:39], 1, v[0:1]
	v_lshl_add_u64 v[8:9], v[36:37], 1, v[0:1]
	v_lshl_add_u64 v[82:83], v[34:35], 1, v[0:1]
	v_lshl_add_u64 v[0:1], v[32:33], 1, v[0:1]
	global_load_dwordx4 v[20:23], v[2:3], off offset:1024
	global_load_dwordx4 v[16:19], v[4:5], off offset:1024
	global_load_dwordx4 v[12:15], v[6:7], off offset:1024
	s_nop 0
	global_load_dwordx4 v[8:11], v[8:9], off offset:1024
	s_nop 0
	global_load_dwordx4 v[4:7], v[82:83], off offset:1024
	s_nop 0
	global_load_dwordx4 v[0:3], v[0:1], off offset:1024
	v_and_b32_e32 v49, 15, v59
	v_lshlrev_b32_e32 v128, 4, v49
	s_waitcnt vmcnt(11)
	v_lshlrev_b32_e32 v55, 16, v28
	v_and_b32_e32 v28, 0xffff0000, v28
	s_waitcnt lgkmcnt(1)
	v_sub_f32_e32 v55, v55, v45
	v_sub_f32_e32 v28, v28, v45
	s_waitcnt lgkmcnt(0)
	v_mul_f32_e32 v55, v46, v55
	v_mul_f32_e32 v28, v46, v28
	s_waitcnt vmcnt(10)
	v_mul_f32_e32 v50, v55, v50
	v_mul_f32_e32 v28, v28, v51
	v_cvt_pk_bf16_f32 v50, 0, v50
	ds_write_b16_d16_hi v47, v50 offset:32768
	v_cvt_pk_bf16_f32 v28, 0, v28
	ds_write_b16_d16_hi v47, v28 offset:32832
	v_lshlrev_b32_e32 v28, 16, v29
	v_sub_f32_e32 v28, v28, v45
	v_mul_f32_e32 v28, v46, v28
	v_mul_f32_e32 v28, v28, v52
	v_cvt_pk_bf16_f32 v28, 0, v28
	ds_write_b16_d16_hi v47, v28 offset:32896
	v_and_b32_e32 v28, 0xffff0000, v29
	v_sub_f32_e32 v28, v28, v45
	v_mul_f32_e32 v28, v46, v28
	v_mul_f32_e32 v28, v28, v53
	v_cvt_pk_bf16_f32 v28, 0, v28
	ds_write_b16_d16_hi v47, v28 offset:32960
	v_lshlrev_b32_e32 v28, 16, v30
	v_sub_f32_e32 v28, v28, v45
	v_mul_f32_e32 v28, v46, v28
	s_waitcnt vmcnt(9)
	v_mul_f32_e32 v28, v28, v70
	v_cvt_pk_bf16_f32 v28, 0, v28
	ds_write_b16_d16_hi v47, v28 offset:33024
	v_and_b32_e32 v28, 0xffff0000, v30
	v_sub_f32_e32 v28, v28, v45
	v_mul_f32_e32 v28, v46, v28
	v_mul_f32_e32 v28, v28, v71
	v_cvt_pk_bf16_f32 v28, 0, v28
	ds_write_b16_d16_hi v47, v28 offset:33088
	v_lshlrev_b32_e32 v28, 16, v31
	v_sub_f32_e32 v30, v28, v45
	v_lshl_add_u64 v[28:29], v[42:43], 2, s[14:15]
	global_load_dwordx4 v[50:53], v[28:29], off offset:16
	global_load_dwordx4 v[82:85], v[28:29], off
	v_mul_f32_e32 v28, v46, v30
	v_mul_f32_e32 v28, v28, v72
	v_cvt_pk_bf16_f32 v28, 0, v28
	ds_write_b16_d16_hi v47, v28 offset:33152
	v_and_b32_e32 v28, 0xffff0000, v31
	v_sub_f32_e32 v28, v28, v45
	v_mul_f32_e32 v28, v46, v28
	v_mul_f32_e32 v28, v28, v73
	v_cvt_pk_bf16_f32 v28, 0, v28
	v_lshl_or_b32 v29, v48, 6, v159
	v_add_u32_e32 v29, v44, v29
	ds_write_b16_d16_hi v29, v28 offset:32768
	s_waitcnt vmcnt(10)
	v_lshlrev_b32_e32 v28, 16, v24
	v_sub_f32_e32 v28, v28, v45
	v_mul_f32_e32 v28, v46, v28
	v_and_b32_e32 v24, 0xffff0000, v24
	s_waitcnt vmcnt(8)
; __device__ __forceinline__ float bflo(unsigned w) { return __uint_as_float(w << 16); }
; __device__ __forceinline__ float bfhi(unsigned w) { return __uint_as_float(w & 0xffff0000u); }
; __device__ void gmlp_item(const Params& p, int layer, int b, int n, int g, char* smem) {
;     ...
; #pragma unroll
;     for (int i = 0; i < 8; ++i) {
;       int q = tid + 256 * i;
;       int st = q & 127, c0 = (q >> 7) * 8;
;       unsigned w[4] = {raw[i].x, raw[i].y, raw[i].z, raw[i].w};
;       float mu = mu_s[st], rs = rs_s[st];
;       const float4* gp = reinterpret_cast<const float4*>(p.gm_gain + (size_t)layer * 512 + g * 128 + c0);
;       float4 g0 = gp[0], g1 = gp[1];
;       float gg[8] = {g0.x, g0.y, g0.z, g0.w, g1.x, g1.y, g1.z, g1.w};
; #pragma unroll
;       for (int e = 0; e < 8; ++e) {
;         float v = (e & 1) ? bfhi(w[e >> 1]) : bflo(w[e >> 1]);
;         float val = (v - mu) * rs * gg[e];
;         *reinterpret_cast<u16*>(smem + 32768 + (st >> 5) * 8192 + (c0 + e) * 64 + (st & 31) * 2) = f2bf(val);
;       }
	v_mul_f32_e32 v28, v28, v78
	v_sub_f32_e32 v24, v24, v45
	v_mul_f32_e32 v24, v46, v24
	v_cvt_pk_bf16_f32 v28, 0, v28
	v_lshl_add_u32 v43, v54, 6, v44
	v_mul_f32_e32 v24, v24, v79
	ds_write_b16_d16_hi v43, v28 offset:32768
	v_cvt_pk_bf16_f32 v24, 0, v24
	ds_write_b16_d16_hi v43, v24 offset:32832
	v_lshlrev_b32_e32 v24, 16, v25
	v_sub_f32_e32 v24, v24, v45
	v_mul_f32_e32 v24, v46, v24
	v_mul_f32_e32 v24, v24, v80
	v_cvt_pk_bf16_f32 v24, 0, v24
	ds_write_b16_d16_hi v43, v24 offset:32896
	v_and_b32_e32 v24, 0xffff0000, v25
	v_sub_f32_e32 v24, v24, v45
	v_mul_f32_e32 v24, v46, v24
	v_mul_f32_e32 v24, v24, v81
	v_cvt_pk_bf16_f32 v24, 0, v24
	ds_write_b16_d16_hi v43, v24 offset:32960
	v_lshlrev_b32_e32 v24, 16, v26
	v_sub_f32_e32 v24, v24, v45
	v_mul_f32_e32 v24, v46, v24
	v_mul_f32_e32 v24, v24, v74
	v_cvt_pk_bf16_f32 v24, 0, v24
	ds_write_b16_d16_hi v43, v24 offset:33024
	v_and_b32_e32 v24, 0xffff0000, v26
	v_sub_f32_e32 v24, v24, v45
	v_mul_f32_e32 v24, v46, v24
	v_mul_f32_e32 v24, v24, v75
	v_cvt_pk_bf16_f32 v24, 0, v24
	ds_write_b16_d16_hi v43, v24 offset:33088
	v_lshlrev_b32_e32 v24, 16, v27
	v_sub_f32_e32 v26, v24, v45
	v_lshl_add_u64 v[24:25], v[40:41], 2, s[14:15]
	global_load_dwordx4 v[28:31], v[24:25], off offset:16
	global_load_dwordx4 v[70:73], v[24:25], off
	v_mul_f32_e32 v24, v46, v26
	v_mul_f32_e32 v24, v24, v76
	v_cvt_pk_bf16_f32 v24, 0, v24
	ds_write_b16_d16_hi v43, v24 offset:33152
	v_and_b32_e32 v24, 0xffff0000, v27
	v_sub_f32_e32 v24, v24, v45
	v_mul_f32_e32 v24, v46, v24
	v_mul_f32_e32 v24, v24, v77
	v_cvt_pk_bf16_f32 v24, 0, v24
	v_lshl_or_b32 v25, v68, 6, v159
	v_add_u32_e32 v25, v44, v25
	ds_write_b16_d16_hi v25, v24 offset:32768
	s_waitcnt vmcnt(9)
	v_lshlrev_b32_e32 v24, 16, v20
	v_sub_f32_e32 v24, v24, v45
	v_mul_f32_e32 v24, v46, v24
	v_and_b32_e32 v20, 0xffff0000, v20
	s_waitcnt vmcnt(2)
	v_mul_f32_e32 v24, v24, v82
	v_sub_f32_e32 v20, v20, v45
	v_mul_f32_e32 v20, v46, v20
	v_cvt_pk_bf16_f32 v24, 0, v24
	v_lshl_add_u32 v41, v42, 6, v44
	v_mul_f32_e32 v20, v20, v83
	ds_write_b16_d16_hi v41, v24 offset:32768
	v_cvt_pk_bf16_f32 v20, 0, v20
	ds_write_b16_d16_hi v41, v20 offset:32832
	v_lshlrev_b32_e32 v20, 16, v21
	v_sub_f32_e32 v20, v20, v45
	v_mul_f32_e32 v20, v46, v20
	v_mul_f32_e32 v20, v20, v84
	v_cvt_pk_bf16_f32 v20, 0, v20
	ds_write_b16_d16_hi v41, v20 offset:32896
	v_and_b32_e32 v20, 0xffff0000, v21
	v_sub_f32_e32 v20, v20, v45
	v_mul_f32_e32 v20, v46, v20
	v_mul_f32_e32 v20, v20, v85
	v_cvt_pk_bf16_f32 v20, 0, v20
	ds_write_b16_d16_hi v41, v20 offset:32960
	v_lshlrev_b32_e32 v20, 16, v22
	v_sub_f32_e32 v20, v20, v45
	v_mul_f32_e32 v20, v46, v20
	v_mul_f32_e32 v20, v20, v50
	v_cvt_pk_bf16_f32 v20, 0, v20
	ds_write_b16_d16_hi v41, v20 offset:33024
	v_and_b32_e32 v20, 0xffff0000, v22
	v_sub_f32_e32 v20, v20, v45
	v_mul_f32_e32 v20, v46, v20
	v_mul_f32_e32 v20, v20, v51
	v_cvt_pk_bf16_f32 v20, 0, v20
	ds_write_b16_d16_hi v41, v20 offset:33088
	v_lshlrev_b32_e32 v20, 16, v23
	v_sub_f32_e32 v22, v20, v45
	v_lshl_add_u64 v[20:21], v[38:39], 2, s[14:15]
	global_load_dwordx4 v[24:27], v[20:21], off offset:16
	global_load_dwordx4 v[74:77], v[20:21], off
	v_mul_f32_e32 v20, v46, v22
	v_mul_f32_e32 v20, v20, v52
	v_cvt_pk_bf16_f32 v20, 0, v20
	ds_write_b16_d16_hi v41, v20 offset:33152
	v_and_b32_e32 v20, 0xffff0000, v23
	v_sub_f32_e32 v20, v20, v45
	v_mul_f32_e32 v20, v46, v20
	v_mul_f32_e32 v20, v20, v53
	v_cvt_pk_bf16_f32 v20, 0, v20
	v_lshl_or_b32 v21, v66, 6, v159
	v_add_u32_e32 v21, v44, v21
	ds_write_b16_d16_hi v21, v20 offset:32768
	v_lshlrev_b32_e32 v20, 16, v16
	v_sub_f32_e32 v20, v20, v45
	v_mul_f32_e32 v20, v46, v20
	v_and_b32_e32 v16, 0xffff0000, v16
	s_waitcnt vmcnt(2)
	v_mul_f32_e32 v20, v20, v70
	v_sub_f32_e32 v16, v16, v45
	v_mul_f32_e32 v16, v46, v16
	v_cvt_pk_bf16_f32 v20, 0, v20
	v_lshl_add_u32 v39, v40, 6, v44
	v_mul_f32_e32 v16, v16, v71
	ds_write_b16_d16_hi v39, v20 offset:32768
	v_cvt_pk_bf16_f32 v16, 0, v16
	ds_write_b16_d16_hi v39, v16 offset:32832
	v_lshlrev_b32_e32 v16, 16, v17
	v_sub_f32_e32 v16, v16, v45
	v_mul_f32_e32 v16, v46, v16
	v_mul_f32_e32 v16, v16, v72
	v_cvt_pk_bf16_f32 v16, 0, v16
	ds_write_b16_d16_hi v39, v16 offset:32896
	v_and_b32_e32 v16, 0xffff0000, v17
	v_sub_f32_e32 v16, v16, v45
	v_mul_f32_e32 v16, v46, v16
	v_mul_f32_e32 v16, v16, v73
	v_cvt_pk_bf16_f32 v16, 0, v16
	ds_write_b16_d16_hi v39, v16 offset:32960
	v_lshlrev_b32_e32 v16, 16, v18
	v_sub_f32_e32 v16, v16, v45
	v_mul_f32_e32 v16, v46, v16
	v_mul_f32_e32 v16, v16, v28
	v_cvt_pk_bf16_f32 v16, 0, v16
	ds_write_b16_d16_hi v39, v16 offset:33024
	v_and_b32_e32 v16, 0xffff0000, v18
	v_sub_f32_e32 v16, v16, v45
	v_mul_f32_e32 v16, v46, v16
	v_mul_f32_e32 v16, v16, v29
	v_cvt_pk_bf16_f32 v16, 0, v16
	ds_write_b16_d16_hi v39, v16 offset:33088
	v_lshlrev_b32_e32 v16, 16, v19
	v_sub_f32_e32 v18, v16, v45
	v_lshl_add_u64 v[16:17], v[36:37], 2, s[14:15]
	global_load_dwordx4 v[20:23], v[16:17], off offset:16
	global_load_dwordx4 v[40:43], v[16:17], off
	v_mul_f32_e32 v16, v46, v18
	v_mul_f32_e32 v16, v16, v30
	v_cvt_pk_bf16_f32 v16, 0, v16
	ds_write_b16_d16_hi v39, v16 offset:33152
	v_and_b32_e32 v16, 0xffff0000, v19
	v_sub_f32_e32 v16, v16, v45
	v_mul_f32_e32 v16, v46, v16
	v_mul_f32_e32 v16, v16, v31
	v_cvt_pk_bf16_f32 v16, 0, v16
	v_lshl_or_b32 v17, v64, 6, v159
	v_add_u32_e32 v17, v44, v17
	ds_write_b16_d16_hi v17, v16 offset:32768
	v_lshlrev_b32_e32 v16, 16, v12
	v_sub_f32_e32 v16, v16, v45
	v_mul_f32_e32 v16, v46, v16
	v_and_b32_e32 v12, 0xffff0000, v12
	s_waitcnt vmcnt(2)
; __device__ __forceinline__ float bflo(unsigned w) { return __uint_as_float(w << 16); }
; __device__ __forceinline__ float bfhi(unsigned w) { return __uint_as_float(w & 0xffff0000u); }
; __device__ void gmlp_item(const Params& p, int layer, int b, int n, int g, char* smem) {
;     ...
; #pragma unroll
;     for (int i = 0; i < 8; ++i) {
;       int q = tid + 256 * i;
;       int st = q & 127, c0 = (q >> 7) * 8;
;       unsigned w[4] = {raw[i].x, raw[i].y, raw[i].z, raw[i].w};
;       float mu = mu_s[st], rs = rs_s[st];
;       const float4* gp = reinterpret_cast<const float4*>(p.gm_gain + (size_t)layer * 512 + g * 128 + c0);
;       float4 g0 = gp[0], g1 = gp[1];
;       float gg[8] = {g0.x, g0.y, g0.z, g0.w, g1.x, g1.y, g1.z, g1.w};
; #pragma unroll
;       for (int e = 0; e < 8; ++e) {
;         float v = (e & 1) ? bfhi(w[e >> 1]) : bflo(w[e >> 1]);
;         float val = (v - mu) * rs * gg[e];
;         *reinterpret_cast<u16*>(smem + 32768 + (st >> 5) * 8192 + (c0 + e) * 64 + (st & 31) * 2) = f2bf(val);
;       }
;     }
;   }
; #pragma unroll 2
;   for (int i = 0; i < 8; ++i) {
;     int q = tid + 256 * i;
;     int t = q >> 4, cch = q & 15;
;     uint4 v = *reinterpret_cast<const uint4*>(Ws + (size_t)g * 16384 + t * 128 + cch * 8);
;     *reinterpret_cast<uint4*>(smem + (cch >> 2) * 8192 + t * 64 + (cch & 3) * 16) = v;
	v_mul_f32_e32 v16, v16, v74
	v_sub_f32_e32 v12, v12, v45
	v_mul_f32_e32 v12, v46, v12
	v_cvt_pk_bf16_f32 v16, 0, v16
	v_lshl_add_u32 v37, v38, 6, v44
	v_mul_f32_e32 v12, v12, v75
	ds_write_b16_d16_hi v37, v16 offset:32768
	v_cvt_pk_bf16_f32 v12, 0, v12
	ds_write_b16_d16_hi v37, v12 offset:32832
	v_lshlrev_b32_e32 v12, 16, v13
	v_sub_f32_e32 v12, v12, v45
	v_mul_f32_e32 v12, v46, v12
	v_mul_f32_e32 v12, v12, v76
	v_cvt_pk_bf16_f32 v12, 0, v12
	ds_write_b16_d16_hi v37, v12 offset:32896
	v_and_b32_e32 v12, 0xffff0000, v13
	v_sub_f32_e32 v12, v12, v45
	v_mul_f32_e32 v12, v46, v12
	v_mul_f32_e32 v12, v12, v77
	v_cvt_pk_bf16_f32 v12, 0, v12
	ds_write_b16_d16_hi v37, v12 offset:32960
	v_lshlrev_b32_e32 v12, 16, v14
	v_sub_f32_e32 v12, v12, v45
	v_mul_f32_e32 v12, v46, v12
	v_mul_f32_e32 v12, v12, v24
	v_cvt_pk_bf16_f32 v12, 0, v12
	ds_write_b16_d16_hi v37, v12 offset:33024
	v_and_b32_e32 v12, 0xffff0000, v14
	v_sub_f32_e32 v12, v12, v45
	v_mul_f32_e32 v12, v46, v12
	v_mul_f32_e32 v12, v12, v25
	v_cvt_pk_bf16_f32 v12, 0, v12
	ds_write_b16_d16_hi v37, v12 offset:33088
	v_lshlrev_b32_e32 v12, 16, v15
	v_sub_f32_e32 v14, v12, v45
	v_lshl_add_u64 v[12:13], v[34:35], 2, s[14:15]
	global_load_dwordx4 v[16:19], v[12:13], off offset:16
	global_load_dwordx4 v[28:31], v[12:13], off
	v_mul_f32_e32 v12, v46, v14
	v_mul_f32_e32 v12, v12, v26
	v_cvt_pk_bf16_f32 v12, 0, v12
	ds_write_b16_d16_hi v37, v12 offset:33152
	v_and_b32_e32 v12, 0xffff0000, v15
	v_sub_f32_e32 v12, v12, v45
	v_mul_f32_e32 v12, v46, v12
	v_mul_f32_e32 v12, v12, v27
	v_cvt_pk_bf16_f32 v12, 0, v12
	v_lshl_or_b32 v13, v62, 6, v159
	v_add_u32_e32 v13, v44, v13
	ds_write_b16_d16_hi v13, v12 offset:32768
	v_lshlrev_b32_e32 v12, 16, v8
	v_sub_f32_e32 v12, v12, v45
	v_mul_f32_e32 v12, v46, v12
	v_and_b32_e32 v8, 0xffff0000, v8
	s_waitcnt vmcnt(2)
	v_mul_f32_e32 v12, v12, v40
	v_sub_f32_e32 v8, v8, v45
	v_mul_f32_e32 v8, v46, v8
	v_cvt_pk_bf16_f32 v12, 0, v12
	v_lshl_add_u32 v35, v36, 6, v44
	v_mul_f32_e32 v8, v8, v41
	ds_write_b16_d16_hi v35, v12 offset:32768
	v_cvt_pk_bf16_f32 v8, 0, v8
	ds_write_b16_d16_hi v35, v8 offset:32832
	v_lshlrev_b32_e32 v8, 16, v9
	v_sub_f32_e32 v8, v8, v45
	v_mul_f32_e32 v8, v46, v8
	v_mul_f32_e32 v8, v8, v42
	v_cvt_pk_bf16_f32 v8, 0, v8
	ds_write_b16_d16_hi v35, v8 offset:32896
	v_and_b32_e32 v8, 0xffff0000, v9
	v_sub_f32_e32 v8, v8, v45
	v_mul_f32_e32 v8, v46, v8
	v_mul_f32_e32 v8, v8, v43
	v_cvt_pk_bf16_f32 v8, 0, v8
	ds_write_b16_d16_hi v35, v8 offset:32960
	v_lshlrev_b32_e32 v8, 16, v10
	v_sub_f32_e32 v8, v8, v45
	v_mul_f32_e32 v8, v46, v8
	v_mul_f32_e32 v8, v8, v20
	v_cvt_pk_bf16_f32 v8, 0, v8
	ds_write_b16_d16_hi v35, v8 offset:33024
	v_and_b32_e32 v8, 0xffff0000, v10
	v_sub_f32_e32 v8, v8, v45
	v_mul_f32_e32 v8, v46, v8
	v_mul_f32_e32 v8, v8, v21
	v_cvt_pk_bf16_f32 v10, 0, v8
	v_lshl_add_u64 v[8:9], v[32:33], 2, s[14:15]
	global_load_dwordx4 v[12:15], v[8:9], off offset:16
	global_load_dwordx4 v[24:27], v[8:9], off
	v_lshlrev_b32_e32 v8, 16, v11
	v_sub_f32_e32 v8, v8, v45
	v_mul_f32_e32 v8, v46, v8
	v_mul_f32_e32 v8, v8, v22
	v_cvt_pk_bf16_f32 v8, 0, v8
	ds_write_b16_d16_hi v35, v8 offset:33152
	v_and_b32_e32 v8, 0xffff0000, v11
	v_sub_f32_e32 v8, v8, v45
	v_mul_f32_e32 v8, v46, v8
	v_mul_f32_e32 v8, v8, v23
	v_cvt_pk_bf16_f32 v8, 0, v8
	v_lshl_or_b32 v9, v60, 6, v159
	v_add_u32_e32 v9, v44, v9
	ds_write_b16_d16_hi v35, v10 offset:33088
	ds_write_b16_d16_hi v9, v8 offset:32768
	v_lshlrev_b32_e32 v8, 16, v4
	v_sub_f32_e32 v8, v8, v45
	v_mul_f32_e32 v8, v46, v8
	v_and_b32_e32 v4, 0xffff0000, v4
	s_waitcnt vmcnt(2)
	v_mul_f32_e32 v8, v8, v28
	v_sub_f32_e32 v4, v4, v45
	v_mul_f32_e32 v4, v46, v4
	v_cvt_pk_bf16_f32 v8, 0, v8
	v_lshl_add_u32 v9, v34, 6, v44
	v_mul_f32_e32 v4, v4, v29
	ds_write_b16_d16_hi v9, v8 offset:32768
	v_cvt_pk_bf16_f32 v4, 0, v4
	ds_write_b16_d16_hi v9, v4 offset:32832
	v_lshlrev_b32_e32 v4, 16, v5
	v_sub_f32_e32 v4, v4, v45
	v_mul_f32_e32 v4, v46, v4
	v_mul_f32_e32 v4, v4, v30
	v_cvt_pk_bf16_f32 v4, 0, v4
	ds_write_b16_d16_hi v9, v4 offset:32896
	v_and_b32_e32 v4, 0xffff0000, v5
	v_sub_f32_e32 v4, v4, v45
	v_mul_f32_e32 v4, v46, v4
	v_mul_f32_e32 v4, v4, v31
	v_cvt_pk_bf16_f32 v4, 0, v4
	ds_write_b16_d16_hi v9, v4 offset:32960
	v_lshlrev_b32_e32 v4, 16, v6
	v_sub_f32_e32 v4, v4, v45
	v_mul_f32_e32 v4, v46, v4
	v_mul_f32_e32 v4, v4, v16
	v_cvt_pk_bf16_f32 v4, 0, v4
	ds_write_b16_d16_hi v9, v4 offset:33024
	v_and_b32_e32 v4, 0xffff0000, v6
	v_sub_f32_e32 v4, v4, v45
	v_mul_f32_e32 v4, v46, v4
	v_mul_f32_e32 v4, v4, v17
	v_cvt_pk_bf16_f32 v4, 0, v4
	ds_write_b16_d16_hi v9, v4 offset:33088
	v_lshlrev_b32_e32 v4, 16, v7
	v_sub_f32_e32 v4, v4, v45
	v_mul_f32_e32 v4, v46, v4
	v_mul_f32_e32 v4, v4, v18
	v_cvt_pk_bf16_f32 v4, 0, v4
	ds_write_b16_d16_hi v9, v4 offset:33152
	v_and_b32_e32 v4, 0xffff0000, v7
	v_sub_f32_e32 v4, v4, v45
	v_mul_f32_e32 v4, v46, v4
	v_mul_f32_e32 v4, v4, v19
	v_cvt_pk_bf16_f32 v4, 0, v4
	v_lshl_or_b32 v5, v58, 6, v159
	v_add_u32_e32 v5, v44, v5
	ds_write_b16_d16_hi v5, v4 offset:32768
	v_lshlrev_b32_e32 v4, 16, v0
	v_sub_f32_e32 v4, v4, v45
	v_mul_f32_e32 v4, v46, v4
	v_and_b32_e32 v0, 0xffff0000, v0
	s_waitcnt vmcnt(0)
	v_mul_f32_e32 v4, v4, v24
	v_sub_f32_e32 v0, v0, v45
	v_mul_f32_e32 v0, v46, v0
	v_cvt_pk_bf16_f32 v4, 0, v4
	v_lshl_add_u32 v5, v32, 6, v44
	v_mul_f32_e32 v0, v0, v25
	ds_write_b16_d16_hi v5, v4 offset:32768
	v_cvt_pk_bf16_f32 v0, 0, v0
	ds_write_b16_d16_hi v5, v0 offset:32832
	v_lshlrev_b32_e32 v0, 16, v1
	v_sub_f32_e32 v0, v0, v45
	v_mul_f32_e32 v0, v46, v0
	v_mul_f32_e32 v0, v0, v26
	v_cvt_pk_bf16_f32 v0, 0, v0
	ds_write_b16_d16_hi v5, v0 offset:32896
	v_and_b32_e32 v0, 0xffff0000, v1
	v_sub_f32_e32 v0, v0, v45
	v_mul_f32_e32 v0, v46, v0
	v_mul_f32_e32 v0, v0, v27
	v_cvt_pk_bf16_f32 v0, 0, v0
	ds_write_b16_d16_hi v5, v0 offset:32960
	v_lshlrev_b32_e32 v0, 16, v2
	v_sub_f32_e32 v0, v0, v45
	v_mul_f32_e32 v0, v46, v0
	v_mul_f32_e32 v0, v0, v12
	v_cvt_pk_bf16_f32 v0, 0, v0
	ds_write_b16_d16_hi v5, v0 offset:33024
	v_and_b32_e32 v0, 0xffff0000, v2
	v_sub_f32_e32 v0, v0, v45
	v_mul_f32_e32 v0, v46, v0
	v_mul_f32_e32 v0, v0, v13
	v_cvt_pk_bf16_f32 v0, 0, v0
	ds_write_b16_d16_hi v5, v0 offset:33088
	v_lshlrev_b32_e32 v0, 16, v3
	v_sub_f32_e32 v0, v0, v45
	v_mul_f32_e32 v0, v46, v0
	v_mul_f32_e32 v0, v0, v14
	v_cvt_pk_bf16_f32 v0, 0, v0
	ds_write_b16_d16_hi v5, v0 offset:33152
	v_and_b32_e32 v0, 0xffff0000, v3
	v_sub_f32_e32 v0, v0, v45
	v_mul_f32_e32 v0, v46, v0
	v_mul_f32_e32 v0, v0, v15
	s_lshl_b32 s14, s20, 15
	v_cvt_pk_bf16_f32 v0, 0, v0
	v_lshl_or_b32 v1, v56, 6, v159
	s_add_u32 s14, s21, s14
	v_add_u32_e32 v1, v44, v1
	s_addc_u32 s15, s48, 0
	v_lshlrev_b32_e32 v3, 4, v59
	ds_write_b16_d16_hi v1, v0 offset:32768
	v_lshl_add_u64 v[0:1], s[14:15], 0, v[128:129]
	v_lshlrev_b32_e32 v2, 11, v59
	v_and_b32_e32 v3, 48, v3
	v_lshl_add_u64 v[0:1], v[0:1], 0, s[38:39]
	v_and_or_b32 v2, v2, s67, v3
	s_mov_b32 s14, 0
; #define MFMA16(a, b, c) __builtin_amdgcn_mfma_f32_16x16x32_bf16(a, b, c, 0, 0, 0)
; __device__ void gmlp_item(const Params& p, int layer, int b, int n, int g, char* smem) {
;     ...
; #pragma unroll 2
;   for (int i = 0; i < 8; ++i) {
;     int q = tid + 256 * i;
;     int t = q >> 4, cch = q & 15;
;     uint4 v = *reinterpret_cast<const uint4*>(Ws + (size_t)g * 16384 + t * 128 + cch * 8);
;     *reinterpret_cast<uint4*>(smem + (cch >> 2) * 8192 + t * 64 + (cch & 3) * 16) = v;
;   }
;   __syncthreads();
;   f32x4 acc[4][4];
; #pragma unroll
;   for (int m = 0; m < 4; ++m)
; #pragma unroll
;     for (int nn = 0; nn < 4; ++nn) acc[m][nn] = f32x4{0.f, 0.f, 0.f, 0.f};
; #pragma unroll
;   for (int ks = 0; ks < 4; ++ks) {
;     bf16x8 a[4], bb[4];
; #pragma unroll
;     for (int m = 0; m < 4; ++m)
;       a[m] = *reinterpret_cast<const bf16x8*>(smem + ks * 8192 + (wr * 64 + m * 16 + fr) * 64 + fq * 16);
; #pragma unroll
;     for (int nn = 0; nn < 4; ++nn)
;       bb[nn] = *reinterpret_cast<const bf16x8*>(smem + 32768 + ks * 8192 + (wc * 64 + nn * 16 + fr) * 64 + fq * 16);
; #pragma unroll
;     for (int m = 0; m < 4; ++m)
; #pragma unroll
;       for (int nn = 0; nn < 4; ++nn) acc[m][nn] = MFMA16(a[m], bb[nn], acc[m][nn]);
;   }
.LBB0_801:
	v_add_u32_e32 v3, s14, v59
	v_ashrrev_i32_e32 v12, 4, v3
	v_add_u32_e32 v3, 0x100, v3
	v_ashrrev_i32_e32 v3, 4, v3
	v_lshlrev_b32_e32 v4, 7, v12
	v_lshlrev_b32_e32 v6, 7, v3
	v_ashrrev_i32_e32 v5, 31, v4
	v_ashrrev_i32_e32 v7, 31, v6
	v_lshl_add_u64 v[4:5], v[4:5], 1, v[0:1]
	v_lshl_add_u64 v[8:9], v[6:7], 1, v[0:1]
	global_load_dwordx4 v[4:7], v[4:5], off
	s_nop 0
	global_load_dwordx4 v[8:11], v[8:9], off
	s_addk_i32 s14, 0x200
	s_cmpk_lg_i32 s14, 0x800
	v_lshl_add_u32 v12, v12, 6, v2
	v_lshl_add_u32 v3, v3, 6, v2
	s_waitcnt vmcnt(1)
	ds_write_b128 v12, v[4:7]
	s_waitcnt vmcnt(0)
	ds_write_b128 v3, v[8:11]
	s_cbranch_scc1 .LBB0_801
	v_bfe_u32 v54, v59, 4, 2
	v_ashrrev_i32_e32 v55, 7, v59
	v_lshlrev_b32_e32 v4, 4, v54
	v_lshlrev_b32_e32 v0, 12, v55
	v_lshlrev_b32_e32 v5, 6, v49
	v_or3_b32 v57, v4, v0, v5
	s_waitcnt lgkmcnt(0)
	s_barrier
	ds_read_b128 v[0:3], v57
	v_bfe_u32 v61, v59, 6, 1
	v_lshlrev_b32_e32 v6, 12, v61
	v_or3_b32 v63, v4, v6, v5
	ds_read_b128 v[4:7], v63 offset:32768
	ds_read_b128 v[8:11], v57 offset:1024
	ds_read_b128 v[12:15], v63 offset:33792
	ds_read_b128 v[24:27], v63 offset:34816
	ds_read_b128 v[28:31], v63 offset:35840
	s_waitcnt lgkmcnt(4)
	v_mfma_f32_16x16x32_bf16 v[16:19], v[0:3], v[4:7], 0
	s_ashr_i32 s14, s17, 31
	s_add_u32 s17, s28, s17
	s_addc_u32 s20, s29, s14
	s_waitcnt lgkmcnt(2)
	v_mfma_f32_16x16x32_bf16 v[20:23], v[0:3], v[12:15], 0
	s_lshl_b32 s14, s16, 2
	s_add_u32 s14, s24, s14
	v_lshlrev_b32_e32 v55, 6, v55
	s_waitcnt lgkmcnt(1)
	v_mfma_f32_16x16x32_bf16 v[36:39], v[0:3], v[24:27], 0
	s_addc_u32 s15, s25, 0
	v_lshl_or_b32 v54, v54, 2, v55
	s_add_u32 s14, s14, 0x1000
	s_waitcnt lgkmcnt(0)
	v_mfma_f32_16x16x32_bf16 v[40:43], v[0:3], v[28:31], 0
	s_addc_u32 s15, s15, 0
	v_ashrrev_i32_e32 v55, 31, v54
	v_lshl_add_u64 v[126:127], v[54:55], 2, s[14:15]
	v_mfma_f32_16x16x32_bf16 v[44:47], v[8:11], v[4:7], 0
	v_or_b32_e32 v130, 32, v54
	v_ashrrev_i32_e32 v131, 31, v130
	v_lshlrev_b32_e32 v49, 2, v49
	v_mfma_f32_16x16x32_bf16 v[50:53], v[8:11], v[12:15], 0
	v_lshl_add_u64 v[130:131], v[130:131], 2, s[14:15]
	v_ashrrev_i32_e32 v69, 31, v68
	v_ashrrev_i32_e32 v67, 31, v66
	v_mfma_f32_16x16x32_bf16 v[70:73], v[8:11], v[24:27], 0
	v_ashrrev_i32_e32 v65, 31, v64
	v_mfma_f32_16x16x32_bf16 v[74:77], v[8:11], v[28:31], 0
	ds_read_b128 v[0:3], v57 offset:2048
	ds_read_b128 v[8:11], v57 offset:3072
	s_waitcnt lgkmcnt(1)
	v_mfma_f32_16x16x32_bf16 v[82:85], v[0:3], v[12:15], 0
	s_waitcnt lgkmcnt(0)
	v_mfma_f32_16x16x32_bf16 v[98:101], v[8:11], v[12:15], 0
	ds_read_b128 v[12:15], v57 offset:8192
	v_mfma_f32_16x16x32_bf16 v[78:81], v[0:3], v[4:7], 0
	v_mfma_f32_16x16x32_bf16 v[86:89], v[0:3], v[24:27], 0
	v_mfma_f32_16x16x32_bf16 v[94:97], v[8:11], v[4:7], 0
	v_mfma_f32_16x16x32_bf16 v[32:35], v[8:11], v[24:27], 0
	ds_read_b128 v[102:105], v63 offset:40960
	ds_read_b128 v[24:27], v57 offset:9216
	ds_read_b128 v[106:109], v63 offset:41984
	ds_read_b128 v[118:121], v63 offset:43008
	ds_read_b128 v[4:7], v63 offset:44032
	v_mfma_f32_16x16x32_bf16 v[90:93], v[0:3], v[28:31], 0
	s_waitcnt lgkmcnt(4)
	v_mfma_f32_16x16x32_bf16 v[110:113], v[12:15], v[102:105], v[16:19]
	s_waitcnt lgkmcnt(2)
	v_mfma_f32_16x16x32_bf16 v[114:117], v[12:15], v[106:109], v[20:23]
	s_waitcnt lgkmcnt(1)
	v_mfma_f32_16x16x32_bf16 v[122:125], v[12:15], v[118:121], v[36:39]
	s_waitcnt lgkmcnt(0)
	v_mfma_f32_16x16x32_bf16 v[134:137], v[12:15], v[4:7], v[40:43]
	ds_read_b128 v[146:149], v57 offset:10240
	ds_read_b128 v[12:15], v57 offset:11264
	v_mfma_f32_16x16x32_bf16 v[0:3], v[8:11], v[28:31], 0
	ds_read_b128 v[150:153], v57 offset:16384
	ds_read_b128 v[162:165], v57 offset:17408
	ds_read_b128 v[166:169], v57 offset:18432
	ds_read_b128 v[8:11], v57 offset:19456
	ds_read_b128 v[36:39], v63 offset:49152
	ds_read_b128 v[28:31], v63 offset:50176
	ds_read_b128 v[20:23], v63 offset:51200
	ds_read_b128 v[16:19], v63 offset:52224
	v_mfma_f32_16x16x32_bf16 v[138:141], v[24:27], v[102:105], v[44:47]
	v_mfma_f32_16x16x32_bf16 v[50:53], v[24:27], v[106:109], v[50:53]
	v_mfma_f32_16x16x32_bf16 v[70:73], v[24:27], v[118:121], v[70:73]
	v_mfma_f32_16x16x32_bf16 v[74:77], v[24:27], v[4:7], v[74:77]
	ds_read_b128 v[170:173], v57 offset:24576
	ds_read_b128 v[174:177], v57 offset:25600
	ds_read_b128 v[178:181], v57 offset:26624
	ds_read_b128 v[24:27], v57 offset:27648
	ds_read_b128 v[182:185], v63 offset:57344
	ds_read_b128 v[186:189], v63 offset:58368
	ds_read_b128 v[44:47], v63 offset:59392
	ds_read_b128 v[40:43], v63 offset:60416
	s_waitcnt lgkmcnt(0)
	v_mfma_f32_16x16x32_bf16 v[78:81], v[146:149], v[102:105], v[78:81]
	s_barrier
; #define MFMA16(a, b, c) __builtin_amdgcn_mfma_f32_16x16x32_bf16(a, b, c, 0, 0, 0)
; __device__ void gmlp_item(const Params& p, int layer, int b, int n, int g, char* smem) {
;     ...
;   for (int ks = 0; ks < 4; ++ks) {
;     bf16x8 a[4], bb[4];
; #pragma unroll
;     for (int m = 0; m < 4; ++m)
;       a[m] = *reinterpret_cast<const bf16x8*>(smem + ks * 8192 + (wr * 64 + m * 16 + fr) * 64 + fq * 16);
; #pragma unroll
;     for (int nn = 0; nn < 4; ++nn)
;       bb[nn] = *reinterpret_cast<const bf16x8*>(smem + 32768 + ks * 8192 + (wc * 64 + nn * 16 + fr) * 64 + fq * 16);
; #pragma unroll
;     for (int m = 0; m < 4; ++m)
; #pragma unroll
;       for (int nn = 0; nn < 4; ++nn) acc[m][nn] = MFMA16(a[m], bb[nn], acc[m][nn]);
;   }
;   __syncthreads();
;   {
;     float* Tf = reinterpret_cast<float*>(smem);
; #pragma unroll
;     for (int m = 0; m < 4; ++m)
; #pragma unroll
;       for (int j = 0; j < 4; ++j) {
;         int t = wr * 64 + m * 16 + fq * 4 + j;
;         float bias = p.gm_b_s[(size_t)layer * 512 + g * 128 + t];
; #pragma unroll
;         for (int nn = 0; nn < 4; ++nn) Tf[t * 132 + wc * 64 + nn * 16 + fr] = acc[m][nn][j] + bias;
;       }
;     __syncthreads();
	global_load_dwordx4 v[190:193], v[130:131], off
	v_mfma_f32_16x16x32_bf16 v[82:85], v[146:149], v[106:109], v[82:85]
	v_ashrrev_i32_e32 v63, 31, v62
	v_mfma_f32_16x16x32_bf16 v[86:89], v[146:149], v[118:121], v[86:89]
	v_mfma_f32_16x16x32_bf16 v[90:93], v[146:149], v[4:7], v[90:93]
	global_load_dwordx4 v[146:149], v[126:127], off
	v_or_b32_e32 v126, 16, v54
	v_ashrrev_i32_e32 v127, 31, v126
	v_lshl_add_u64 v[126:127], v[126:127], 2, s[14:15]
	v_mfma_f32_16x16x32_bf16 v[110:113], v[150:153], v[36:39], v[110:113]
	v_mfma_f32_16x16x32_bf16 v[114:117], v[150:153], v[28:31], v[114:117]
	v_mfma_f32_16x16x32_bf16 v[122:125], v[150:153], v[20:23], v[122:125]
	v_mfma_f32_16x16x32_bf16 v[134:137], v[150:153], v[16:19], v[134:137]
	global_load_dwordx4 v[150:153], v[126:127], off
	v_lshl_or_b32 v126, v61, 8, v49
	v_mad_u64_u32 v[126:127], s[48:49], v54, s69, v[126:127]
	v_mfma_f32_16x16x32_bf16 v[110:113], v[170:173], v[182:185], v[110:113]
	v_add_u32_e32 v57, 0x400, v126
	v_or_b32_e32 v54, 48, v54
	v_ashrrev_i32_e32 v61, 31, v60
	v_mfma_f32_16x16x32_bf16 v[114:117], v[170:173], v[186:189], v[114:117]
	v_mfma_f32_16x16x32_bf16 v[122:125], v[170:173], v[44:47], v[122:125]
	s_waitcnt vmcnt(1)
	s_nop 1
	v_add_f32_e32 v49, v110, v146
	v_mfma_f32_16x16x32_bf16 v[134:137], v[170:173], v[40:43], v[134:137]
	s_nop 1
	v_add_f32_e32 v55, v114, v146
	ds_write2_b32 v126, v49, v55 offset1:16
	v_add_f32_e32 v49, v122, v146
	v_mfma_f32_16x16x32_bf16 v[98:101], v[12:15], v[106:109], v[98:101]
	v_mfma_f32_16x16x32_bf16 v[94:97], v[12:15], v[102:105], v[94:97]
	s_nop 0
	v_add_f32_e32 v55, v134, v146
	ds_write2_b32 v126, v49, v55 offset0:32 offset1:48
	v_add_f32_e32 v49, v111, v147
	v_add_f32_e32 v55, v115, v147
	ds_write2_b32 v126, v49, v55 offset0:132 offset1:148
	v_add_f32_e32 v49, v123, v147
	v_add_f32_e32 v55, v135, v147
	ds_write2_b32 v126, v49, v55 offset0:164 offset1:180
	v_add_f32_e32 v49, v112, v148
	v_add_f32_e32 v55, v116, v148
	ds_write2_b32 v57, v49, v55 offset0:8 offset1:24
	v_add_f32_e32 v49, v124, v148
	v_add_f32_e32 v55, v136, v148
	ds_write2_b32 v57, v49, v55 offset0:40 offset1:56
	v_add_f32_e32 v49, v113, v149
	v_add_f32_e32 v55, v117, v149
	ds_write2_b32 v57, v49, v55 offset0:140 offset1:156
	v_add_f32_e32 v49, v125, v149
	v_add_f32_e32 v55, v137, v149
	ds_write2_b32 v57, v49, v55 offset0:172 offset1:188
	v_ashrrev_i32_e32 v55, 31, v54
	v_lshl_add_u64 v[54:55], v[54:55], 2, s[14:15]
	global_load_dwordx4 v[106:109], v[54:55], off
	v_mfma_f32_16x16x32_bf16 v[102:105], v[162:165], v[36:39], v[138:141]
	v_add_u32_e32 v54, 0x2000, v126
	v_ashrrev_i32_e32 v57, 31, v56
	v_mfma_f32_16x16x32_bf16 v[50:53], v[162:165], v[28:31], v[50:53]
	v_mfma_f32_16x16x32_bf16 v[70:73], v[162:165], v[20:23], v[70:73]
	v_mfma_f32_16x16x32_bf16 v[74:77], v[162:165], v[16:19], v[74:77]
	v_mfma_f32_16x16x32_bf16 v[102:105], v[174:177], v[182:185], v[102:105]
	v_mfma_f32_16x16x32_bf16 v[50:53], v[174:177], v[186:189], v[50:53]
	v_mfma_f32_16x16x32_bf16 v[70:73], v[174:177], v[44:47], v[70:73]
	s_waitcnt vmcnt(1)
	s_nop 4
	v_add_f32_e32 v49, v102, v150
	v_add_f32_e32 v50, v50, v150
	ds_write2_b32 v54, v49, v50 offset0:64 offset1:80
	v_mfma_f32_16x16x32_bf16 v[74:77], v[174:177], v[40:43], v[74:77]
	v_add_f32_e32 v55, v53, v153
	v_add_f32_e32 v49, v70, v150
	v_mfma_f32_16x16x32_bf16 v[78:81], v[166:169], v[36:39], v[78:81]
	v_mfma_f32_16x16x32_bf16 v[82:85], v[166:169], v[28:31], v[82:85]
	s_nop 3
	v_add_f32_e32 v50, v74, v150
	ds_write2_b32 v54, v49, v50 offset0:96 offset1:112
	v_add_f32_e32 v49, v103, v151
	v_add_f32_e32 v50, v51, v151
	ds_write2_b32 v54, v49, v50 offset0:196 offset1:212
	v_add_f32_e32 v49, v71, v151
	v_add_f32_e32 v50, v75, v151
	ds_write2_b32 v54, v49, v50 offset0:228 offset1:244
	v_add_f32_e32 v49, v104, v152
	v_add_f32_e32 v50, v52, v152
	v_add_u32_e32 v54, 0x2400, v126
	v_mfma_f32_16x16x32_bf16 v[86:89], v[166:169], v[20:23], v[86:89]
	ds_write2_b32 v54, v49, v50 offset0:72 offset1:88
	v_add_f32_e32 v49, v72, v152
	v_add_f32_e32 v50, v76, v152
	v_mfma_f32_16x16x32_bf16 v[90:93], v[166:169], v[16:19], v[90:93]
	ds_write2_b32 v54, v49, v50 offset0:104 offset1:120
	v_add_f32_e32 v49, v105, v153
	ds_write2_b32 v54, v49, v55 offset0:204 offset1:220
	v_mfma_f32_16x16x32_bf16 v[50:53], v[178:181], v[182:185], v[78:81]
	v_add_f32_e32 v49, v73, v153
	v_add_f32_e32 v55, v77, v153
	ds_write2_b32 v54, v49, v55 offset0:236 offset1:252
	v_mfma_f32_16x16x32_bf16 v[70:73], v[178:181], v[186:189], v[82:85]
	v_add_u32_e32 v54, 0x4000, v126
	s_nop 2
	v_add_f32_e32 v49, v50, v190
	v_mfma_f32_16x16x32_bf16 v[74:77], v[178:181], v[44:47], v[86:89]
	v_mfma_f32_16x16x32_bf16 v[78:81], v[178:181], v[40:43], v[90:93]
	s_nop 0
	v_add_f32_e32 v50, v70, v190
	ds_write2_b32 v54, v49, v50 offset0:128 offset1:144
	s_nop 3
	v_add_f32_e32 v49, v74, v190
	v_mfma_f32_16x16x32_bf16 v[32:35], v[12:15], v[118:121], v[32:35]
	v_mfma_f32_16x16x32_bf16 v[0:3], v[12:15], v[4:7], v[0:3]
	v_add_f32_e32 v50, v78, v190
	ds_write2_b32 v54, v49, v50 offset0:160 offset1:176
	v_add_f32_e32 v49, v51, v191
	v_add_f32_e32 v4, v71, v191
	v_add_u32_e32 v50, 0x4400, v126
	v_add_f32_e32 v12, v75, v191
	v_add_f32_e32 v13, v79, v191
	ds_write2_b32 v50, v49, v4 offset0:4 offset1:20
	v_mfma_f32_16x16x32_bf16 v[4:7], v[8:11], v[36:39], v[94:97]
	ds_write2_b32 v50, v12, v13 offset0:36 offset1:52
	v_ashrrev_i32_e32 v49, 31, v48
	v_lshl_add_u64 v[70:71], v[56:57], 0, s[36:37]
	v_mfma_f32_16x16x32_bf16 v[12:15], v[8:11], v[28:31], v[98:101]
	v_add_f32_e32 v28, v52, v192
	v_add_f32_e32 v29, v72, v192
	ds_write2_b32 v50, v28, v29 offset0:136 offset1:152
	v_mfma_f32_16x16x32_bf16 v[20:23], v[8:11], v[20:23], v[32:35]
	v_add_f32_e32 v28, v76, v192
	v_add_f32_e32 v29, v80, v192
	ds_write2_b32 v50, v28, v29 offset0:168 offset1:184
	v_mfma_f32_16x16x32_bf16 v[0:3], v[8:11], v[16:19], v[0:3]
	v_add_f32_e32 v8, v53, v193
	v_add_f32_e32 v9, v73, v193
	v_add_u32_e32 v16, 0x4800, v126
	v_mfma_f32_16x16x32_bf16 v[4:7], v[24:27], v[182:185], v[4:7]
	ds_write2_b32 v16, v8, v9 offset0:12 offset1:28
	v_add_f32_e32 v17, v77, v193
	v_add_f32_e32 v18, v81, v193
	v_mfma_f32_16x16x32_bf16 v[8:11], v[24:27], v[186:189], v[12:15]
	ds_write2_b32 v16, v17, v18 offset0:44 offset1:60
	s_waitcnt vmcnt(0)
; __device__ void gmlp_item(const Params& p, int layer, int b, int n, int g, char* smem) {
;     ...
;   {
;     float* Tf = reinterpret_cast<float*>(smem);
; #pragma unroll
;     for (int m = 0; m < 4; ++m)
; #pragma unroll
;       for (int j = 0; j < 4; ++j) {
;         int t = wr * 64 + m * 16 + fq * 4 + j;
;         float bias = p.gm_b_s[(size_t)layer * 512 + g * 128 + t];
; #pragma unroll
;         for (int nn = 0; nn < 4; ++nn) Tf[t * 132 + wc * 64 + nn * 16 + fr] = acc[m][nn][j] + bias;
;       }
;     __syncthreads();
;     uint4 uu[8], gt[8];
; #pragma unroll
;     for (int i = 0; i < 8; ++i) {
;       int q = tid + 256 * i, t = q >> 4, c = (q & 15) * 8;
;       uu[i] = *reinterpret_cast<const uint4*>(P + (t0 + t) * NP + g * 128 + c);
;       gt[i] = *reinterpret_cast<const uint4*>(P + (t0 + t) * NP + 1024 + g * 128 + c);
;     }
	s_nop 1
	v_add_f32_e32 v4, v4, v106
	v_add_u32_e32 v16, 0x6000, v126
	v_mfma_f32_16x16x32_bf16 v[12:15], v[24:27], v[44:47], v[20:23]
	v_lshl_add_u64 v[36:37], v[62:63], 0, s[36:37]
	v_add_f32_e32 v8, v8, v106
	ds_write2_b32 v16, v4, v8 offset0:192 offset1:208
	v_mfma_f32_16x16x32_bf16 v[0:3], v[24:27], v[40:43], v[0:3]
	v_lshl_add_u64 v[20:21], v[64:65], 0, s[36:37]
	s_nop 2
	v_add_f32_e32 v4, v12, v106
	v_lshl_add_u64 v[38:39], v[60:61], 0, s[36:37]
	s_nop 1
	v_add_f32_e32 v0, v0, v106
	ds_write2_b32 v16, v4, v0 offset0:224 offset1:240
	v_add_f32_e32 v0, v5, v107
	v_add_f32_e32 v4, v9, v107
	v_add_u32_e32 v5, 0x6400, v126
	ds_write2_b32 v5, v0, v4 offset0:68 offset1:84
	v_add_f32_e32 v0, v13, v107
	v_add_f32_e32 v1, v1, v107
	ds_write2_b32 v5, v0, v1 offset0:100 offset1:116
	v_add_f32_e32 v0, v6, v108
	v_add_f32_e32 v1, v10, v108
	ds_write2_b32 v5, v0, v1 offset0:200 offset1:216
	v_add_f32_e32 v0, v14, v108
	v_add_f32_e32 v1, v2, v108
	ds_write2_b32 v5, v0, v1 offset0:232 offset1:248
	v_add_f32_e32 v0, v7, v109
	v_add_f32_e32 v1, v11, v109
	v_add_u32_e32 v2, 0x6800, v126
	ds_write2_b32 v2, v0, v1 offset0:76 offset1:92
	v_add_f32_e32 v0, v15, v109
	v_add_f32_e32 v1, v3, v109
	ds_write2_b32 v2, v0, v1 offset0:108 offset1:124
	v_lshlrev_b32_e32 v0, 3, v59
	v_lshl_add_u64 v[8:9], v[48:49], 0, s[36:37]
	v_mov_b64_e32 v[10:11], s[12:13]
	v_and_b32_e32 v24, 0x78, v0
	v_mad_u64_u32 v[0:1], s[12:13], v8, s45, v[10:11]
	v_mad_i32_i24 v1, v9, s45, v1
	s_lshl_b32 s12, s16, 1
	s_mov_b32 s13, s37
	v_lshl_add_u64 v[0:1], v[0:1], 0, s[12:13]
	v_lshlrev_b32_e32 v128, 1, v24
	v_lshl_add_u64 v[12:13], v[68:69], 0, s[36:37]
	v_lshl_add_u64 v[52:53], v[0:1], 0, v[128:129]
	v_mad_u64_u32 v[0:1], s[14:15], v12, s45, v[10:11]
	v_mad_i32_i24 v1, v13, s45, v1
	v_lshl_add_u64 v[0:1], v[0:1], 0, s[12:13]
	v_lshl_add_u64 v[32:33], v[0:1], 0, v[128:129]
	v_mad_u64_u32 v[0:1], s[14:15], v70, s45, v[10:11]
	v_mad_i32_i24 v1, v71, s45, v1
	v_lshl_add_u64 v[0:1], v[0:1], 0, s[12:13]
	v_lshl_add_u64 v[4:5], v[0:1], 0, v[128:129]
	s_waitcnt lgkmcnt(0)
	s_barrier
	global_load_dwordx4 v[0:3], v[4:5], off
	s_nop 0
	global_load_dwordx4 v[4:7], v[4:5], off offset:2048
	v_lshl_add_u64 v[16:17], v[66:67], 0, s[36:37]
	v_mad_u64_u32 v[14:15], s[14:15], v16, s45, v[10:11]
	v_mad_i32_i24 v15, v17, s45, v15
	v_lshl_add_u64 v[14:15], v[14:15], 0, s[12:13]
	v_lshl_add_u64 v[30:31], v[14:15], 0, v[128:129]
	v_mad_u64_u32 v[14:15], s[14:15], v20, s45, v[10:11]
	v_mad_i32_i24 v15, v21, s45, v15
	v_lshl_add_u64 v[14:15], v[14:15], 0, s[12:13]
	v_lshl_add_u64 v[26:27], v[14:15], 0, v[128:129]
	v_mad_u64_u32 v[14:15], s[14:15], v36, s45, v[10:11]
	v_mad_i32_i24 v15, v37, s45, v15
	v_ashrrev_i32_e32 v59, 31, v58
	v_lshl_add_u64 v[14:15], v[14:15], 0, s[12:13]
	v_lshl_add_u64 v[72:73], v[58:59], 0, s[36:37]
	v_lshl_add_u64 v[22:23], v[14:15], 0, v[128:129]
	v_mad_u64_u32 v[14:15], s[14:15], v38, s45, v[10:11]
	v_mad_u64_u32 v[10:11], s[14:15], v72, s45, v[10:11]
	v_mad_i32_i24 v15, v39, s45, v15
	v_mad_i32_i24 v11, v73, s45, v11
	v_lshl_add_u64 v[14:15], v[14:15], 0, s[12:13]
	v_lshl_add_u64 v[10:11], v[10:11], 0, s[12:13]
	s_add_u32 s12, s17, s12
	s_addc_u32 s13, s20, 0
	v_lshl_add_u64 v[18:19], v[14:15], 0, v[128:129]
	v_lshl_add_u64 v[14:15], v[10:11], 0, v[128:129]
	v_lshlrev_b32_e32 v10, 2, v24
	v_lshl_add_u64 v[24:25], s[12:13], 0, v[128:129]
	v_lshl_add_u64 v[74:75], v[24:25], 0, s[40:41]
	v_mad_u64_u32 v[54:55], s[12:13], v48, s69, v[10:11]
	v_mad_u64_u32 v[48:49], s[12:13], v12, s70, v[74:75]
	v_mad_u64_u32 v[46:47], s[12:13], v16, s70, v[74:75]
	v_mad_u64_u32 v[50:51], s[12:13], v8, s70, v[74:75]
	v_mad_i32_i24 v49, v13, s70, v49
	v_mad_i32_i24 v47, v17, s70, v47
	v_mad_u64_u32 v[44:45], s[12:13], v20, s70, v[74:75]
	v_mad_u64_u32 v[16:17], s[12:13], v60, s69, v[10:11]
	v_mad_u64_u32 v[12:13], s[12:13], v58, s69, v[10:11]
	v_mad_i32_i24 v51, v9, s70, v51
	v_mad_i32_i24 v45, v21, s70, v45
	v_mad_u64_u32 v[20:21], s[12:13], v62, s69, v[10:11]
	v_mad_u64_u32 v[8:9], s[12:13], v56, s69, v[10:11]
	v_mad_u64_u32 v[28:29], s[12:13], v66, s69, v[10:11]
	v_mad_u64_u32 v[34:35], s[12:13], v68, s69, v[10:11]
	v_mad_u64_u32 v[24:25], s[12:13], v64, s69, v[10:11]
	v_mad_u64_u32 v[42:43], s[12:13], v36, s70, v[74:75]
	v_mad_i32_i24 v43, v37, s70, v43
	v_mad_u64_u32 v[36:37], s[12:13], v70, s70, v[74:75]
	v_mad_u64_u32 v[40:41], s[12:13], v38, s70, v[74:75]
	v_mad_i32_i24 v41, v39, s70, v41
	v_mad_u64_u32 v[38:39], s[12:13], v72, s70, v[74:75]
	v_mad_i32_i24 v39, v73, s70, v39
	v_mad_i32_i24 v37, v71, s70, v37
	s_waitcnt vmcnt(1)
	v_lshlrev_b32_e32 v63, 16, v1
	s_waitcnt vmcnt(0)
	v_lshlrev_b32_e32 v13, 16, v5
	v_lshlrev_b32_e32 v17, 16, v4
	v_mul_f32_e32 v9, 0xbfb8aa3b, v17
	v_and_b32_e32 v21, 0xffff0000, v5
	v_mul_f32_e32 v5, 0xbfb8aa3b, v13
	v_exp_f32_e32 v60, v9
	v_exp_f32_e32 v61, v5
	ds_read_b128 v[56:59], v8
	ds_read_b128 v[8:11], v8 offset:16
	v_and_b32_e32 v25, 0xffff0000, v4
	v_mul_f32_e32 v4, 0xbfb8aa3b, v25
	v_pk_add_f32 v[60:61], v[60:61], 1.0 op_sel_hi:[1,0]
	s_waitcnt lgkmcnt(1)
; __device__ __forceinline__ unsigned pack2(float a, float b) { return (unsigned)f2bf(a) | ((unsigned)f2bf(b) << 16); }
; __device__ __forceinline__ float bflo(unsigned w) { return __uint_as_float(w << 16); }
; __device__ __forceinline__ float bfhi(unsigned w) { return __uint_as_float(w & 0xffff0000u); }
; __device__ __forceinline__ float silu_f(float g) { return g / (1.f + __expf(-g)); }
; __device__ void gmlp_item(const Params& p, int layer, int b, int n, int g, char* smem) {
;     ...
; #pragma unroll
;     for (int i = 0; i < 8; ++i) {
;       int q = tid + 256 * i, t = q >> 4, c = (q & 15) * 8;
;       float4 m0 = *reinterpret_cast<const float4*>(Tf + t * 132 + c);
;       float4 m1 = *reinterpret_cast<const float4*>(Tf + t * 132 + c + 4);
;       float mm[8] = {m0.x, m0.y, m0.z, m0.w, m1.x, m1.y, m1.z, m1.w};
;       unsigned uw[4] = {uu[i].x, uu[i].y, uu[i].z, uu[i].w};
;       unsigned gw[4] = {gt[i].x, gt[i].y, gt[i].z, gt[i].w};
;       unsigned ow[4];
; #pragma unroll
;       for (int e = 0; e < 4; ++e) {
;         float y0 = bflo(uw[e]) * mm[2 * e] * silu_f(bflo(gw[e]));
;         float y1 = bfhi(uw[e]) * mm[2 * e + 1] * silu_f(bfhi(gw[e]));
;         ow[e] = pack2(y0, y1);
;       }
;       *reinterpret_cast<uint4*>(Y + (t0 + t) * YW + g * 128 + c) = make_uint4(ow[0], ow[1], ow[2], ow[3]);
	v_mov_b32_e32 v64, v56
	v_exp_f32_e32 v4, v4
	v_lshlrev_b32_e32 v62, 16, v0
	v_mov_b32_e32 v65, v58
	v_rcp_f32_e32 v61, v61
	s_nop 0
	v_mul_f32_e32 v61, v13, v61
	v_and_b32_e32 v1, 0xffff0000, v1
	v_mul_f32_e32 v5, 0xbfb8aa3b, v21
	v_exp_f32_e32 v5, v5
	v_rcp_f32_e32 v60, v60
	s_nop 0
	v_mul_f32_e32 v60, v17, v60
	v_and_b32_e32 v0, 0xffff0000, v0
	v_mov_b32_e32 v58, v57
	v_pk_add_f32 v[4:5], v[4:5], 1.0 op_sel_hi:[1,0]
	v_pk_mul_f32 v[0:1], v[58:59], v[0:1]
	v_pk_mul_f32 v[62:63], v[64:65], v[62:63]
	v_rcp_f32_e32 v5, v5
	s_nop 0
	v_mul_f32_e32 v5, v21, v5
	v_pk_mul_f32 v[60:61], v[60:61], v[62:63]
	v_rcp_f32_e32 v4, v4
	s_nop 0
	v_mul_f32_e32 v4, v25, v4
	v_pk_mul_f32 v[0:1], v[4:5], v[0:1]
	v_cvt_pk_bf16_f32 v1, 0, v1
	v_cvt_pk_bf16_f32 v0, 0, v0
	v_cvt_pk_bf16_f32 v5, 0, v60
	v_cvt_pk_bf16_f32 v4, 0, v61
	v_and_b32_e32 v1, 0xffff0000, v1
	v_and_b32_e32 v0, 0xffff0000, v0
	v_lshlrev_b32_e32 v13, 16, v7
	v_lshlrev_b32_e32 v17, 16, v6
	v_or_b32_sdwa v1, v1, v4 dst_sel:DWORD dst_unused:UNUSED_PAD src0_sel:DWORD src1_sel:WORD_1
	v_or_b32_sdwa v0, v0, v5 dst_sel:DWORD dst_unused:UNUSED_PAD src0_sel:DWORD src1_sel:WORD_1
	v_mul_f32_e32 v4, 0xbfb8aa3b, v17
	v_mul_f32_e32 v5, 0xbfb8aa3b, v13
	v_exp_f32_e32 v4, v4
	v_exp_f32_e32 v5, v5
	v_and_b32_e32 v25, 0xffff0000, v6
	v_mul_f32_e32 v6, 0xbfb8aa3b, v25
	v_and_b32_e32 v21, 0xffff0000, v7
	v_exp_f32_e32 v60, v6
	v_pk_add_f32 v[64:65], v[4:5], 1.0 op_sel_hi:[1,0]
	global_load_dwordx4 v[4:7], v[14:15], off
	global_load_dwordx4 v[56:59], v[14:15], off offset:2048
	s_waitcnt lgkmcnt(0)
	v_mov_b32_e32 v14, v8
	v_mov_b32_e32 v15, v10
	v_lshlrev_b32_e32 v63, 16, v3
	v_lshlrev_b32_e32 v62, 16, v2
	v_pk_mul_f32 v[14:15], v[14:15], v[62:63]
	v_rcp_f32_e32 v63, v65
	s_nop 0
	v_mul_f32_e32 v63, v13, v63
	v_mul_f32_e32 v10, 0xbfb8aa3b, v21
	v_exp_f32_e32 v61, v10
	v_rcp_f32_e32 v62, v64
	s_nop 0
	v_mul_f32_e32 v62, v17, v62
	v_mov_b32_e32 v10, v9
	v_and_b32_e32 v3, 0xffff0000, v3
	v_pk_add_f32 v[60:61], v[60:61], 1.0 op_sel_hi:[1,0]
	v_and_b32_e32 v2, 0xffff0000, v2
	v_pk_mul_f32 v[2:3], v[10:11], v[2:3]
	v_pk_mul_f32 v[14:15], v[62:63], v[14:15]
	v_rcp_f32_e32 v9, v61
	s_nop 0
	v_mul_f32_e32 v9, v21, v9
	v_rcp_f32_e32 v8, v60
	s_nop 0
	v_mul_f32_e32 v8, v25, v8
	v_pk_mul_f32 v[2:3], v[8:9], v[2:3]
	v_cvt_pk_bf16_f32 v3, 0, v3
	v_cvt_pk_bf16_f32 v8, 0, v15
	v_and_b32_e32 v3, 0xffff0000, v3
	v_or_b32_sdwa v3, v3, v8 dst_sel:DWORD dst_unused:UNUSED_PAD src0_sel:DWORD src1_sel:WORD_1
	v_cvt_pk_bf16_f32 v2, 0, v2
	v_cvt_pk_bf16_f32 v9, 0, v14
	v_and_b32_e32 v2, 0xffff0000, v2
	v_or_b32_sdwa v2, v2, v9 dst_sel:DWORD dst_unused:UNUSED_PAD src0_sel:DWORD src1_sel:WORD_1
	s_waitcnt vmcnt(0)
	v_lshlrev_b32_e32 v21, 16, v56
	v_mul_f32_e32 v8, 0xbfb8aa3b, v21
	v_and_b32_e32 v29, 0xffff0000, v56
	v_lshlrev_b32_e32 v17, 16, v57
	v_exp_f32_e32 v60, v8
	v_mul_f32_e32 v8, 0xbfb8aa3b, v29
	v_exp_f32_e32 v56, v8
	v_mul_f32_e32 v8, 0xbfb8aa3b, v17
	v_exp_f32_e32 v61, v8
	ds_read_b128 v[8:11], v12
	ds_read_b128 v[12:15], v12 offset:16
	v_and_b32_e32 v25, 0xffff0000, v57
	v_lshlrev_b32_e32 v63, 16, v5
	v_pk_add_f32 v[60:61], v[60:61], 1.0 op_sel_hi:[1,0]
	s_waitcnt lgkmcnt(1)
	v_mov_b32_e32 v64, v8
	v_mov_b32_e32 v65, v10
	v_lshlrev_b32_e32 v62, 16, v4
	v_and_b32_e32 v5, 0xffff0000, v5
	v_rcp_f32_e32 v61, v61
	s_nop 0
	v_mul_f32_e32 v61, v17, v61
	v_and_b32_e32 v4, 0xffff0000, v4
	v_mul_f32_e32 v10, 0xbfb8aa3b, v25
	v_exp_f32_e32 v57, v10
	v_rcp_f32_e32 v60, v60
	s_nop 0
	v_mul_f32_e32 v60, v21, v60
	v_mov_b32_e32 v10, v9
	v_pk_mul_f32 v[4:5], v[10:11], v[4:5]
	v_pk_add_f32 v[56:57], v[56:57], 1.0 op_sel_hi:[1,0]
	v_pk_mul_f32 v[62:63], v[64:65], v[62:63]
	v_pk_mul_f32 v[60:61], v[60:61], v[62:63]
	v_lshlrev_b32_e32 v63, 16, v7
	v_lshlrev_b32_e32 v62, 16, v6
	v_rcp_f32_e32 v9, v57
	s_nop 0
	v_mul_f32_e32 v9, v25, v9
	v_rcp_f32_e32 v8, v56
	s_nop 0
	v_mul_f32_e32 v8, v29, v8
	v_pk_mul_f32 v[4:5], v[8:9], v[4:5]
	v_cvt_pk_bf16_f32 v5, 0, v5
	v_cvt_pk_bf16_f32 v4, 0, v4
	v_cvt_pk_bf16_f32 v9, 0, v60
	v_cvt_pk_bf16_f32 v8, 0, v61
	v_and_b32_e32 v5, 0xffff0000, v5
	v_and_b32_e32 v4, 0xffff0000, v4
	v_lshlrev_b32_e32 v17, 16, v59
	v_lshlrev_b32_e32 v21, 16, v58
	v_or_b32_sdwa v5, v5, v8 dst_sel:DWORD dst_unused:UNUSED_PAD src0_sel:DWORD src1_sel:WORD_1
	v_or_b32_sdwa v4, v4, v9 dst_sel:DWORD dst_unused:UNUSED_PAD src0_sel:DWORD src1_sel:WORD_1
	v_mul_f32_e32 v8, 0xbfb8aa3b, v21
	v_mul_f32_e32 v9, 0xbfb8aa3b, v17
	v_exp_f32_e32 v8, v8
	v_exp_f32_e32 v9, v9
	v_and_b32_e32 v29, 0xffff0000, v58
	v_mul_f32_e32 v10, 0xbfb8aa3b, v29
	v_and_b32_e32 v25, 0xffff0000, v59
	v_exp_f32_e32 v60, v10
	v_pk_add_f32 v[64:65], v[8:9], 1.0 op_sel_hi:[1,0]
	global_load_dwordx4 v[8:11], v[18:19], off
	global_load_dwordx4 v[56:59], v[18:19], off offset:2048
	s_waitcnt lgkmcnt(0)
	v_mov_b32_e32 v18, v12
	v_mov_b32_e32 v19, v14
	v_pk_mul_f32 v[18:19], v[18:19], v[62:63]
	v_rcp_f32_e32 v63, v65
	s_nop 0
	v_mul_f32_e32 v63, v17, v63
	v_and_b32_e32 v7, 0xffff0000, v7
	v_mul_f32_e32 v14, 0xbfb8aa3b, v25
	v_exp_f32_e32 v61, v14
	v_rcp_f32_e32 v62, v64
	s_nop 0
	v_mul_f32_e32 v62, v21, v62
	v_mov_b32_e32 v14, v13
	v_and_b32_e32 v6, 0xffff0000, v6
	v_pk_add_f32 v[60:61], v[60:61], 1.0 op_sel_hi:[1,0]
	v_pk_mul_f32 v[6:7], v[14:15], v[6:7]
	v_pk_mul_f32 v[18:19], v[62:63], v[18:19]
	v_rcp_f32_e32 v13, v61
	s_nop 0
	v_mul_f32_e32 v13, v25, v13
	v_rcp_f32_e32 v12, v60
	s_nop 0
	v_mul_f32_e32 v12, v29, v12
	v_pk_mul_f32 v[6:7], v[12:13], v[6:7]
	v_cvt_pk_bf16_f32 v7, 0, v7
	v_cvt_pk_bf16_f32 v12, 0, v19
	v_and_b32_e32 v7, 0xffff0000, v7
	v_or_b32_sdwa v7, v7, v12 dst_sel:DWORD dst_unused:UNUSED_PAD src0_sel:DWORD src1_sel:WORD_1
	v_cvt_pk_bf16_f32 v6, 0, v6
	v_cvt_pk_bf16_f32 v13, 0, v18
	v_and_b32_e32 v6, 0xffff0000, v6
	v_or_b32_sdwa v6, v6, v13 dst_sel:DWORD dst_unused:UNUSED_PAD src0_sel:DWORD src1_sel:WORD_1
	s_waitcnt vmcnt(1)
; __device__ __forceinline__ unsigned pack2(float a, float b) { return (unsigned)f2bf(a) | ((unsigned)f2bf(b) << 16); }
; __device__ __forceinline__ float bflo(unsigned w) { return __uint_as_float(w << 16); }
; __device__ __forceinline__ float bfhi(unsigned w) { return __uint_as_float(w & 0xffff0000u); }
; __device__ __forceinline__ float silu_f(float g) { return g / (1.f + __expf(-g)); }
; __device__ void gmlp_item(const Params& p, int layer, int b, int n, int g, char* smem) {
;     ...
; #pragma unroll
;     for (int i = 0; i < 8; ++i) {
;       int q = tid + 256 * i, t = q >> 4, c = (q & 15) * 8;
;       float4 m0 = *reinterpret_cast<const float4*>(Tf + t * 132 + c);
;       float4 m1 = *reinterpret_cast<const float4*>(Tf + t * 132 + c + 4);
;       float mm[8] = {m0.x, m0.y, m0.z, m0.w, m1.x, m1.y, m1.z, m1.w};
;       unsigned uw[4] = {uu[i].x, uu[i].y, uu[i].z, uu[i].w};
;       unsigned gw[4] = {gt[i].x, gt[i].y, gt[i].z, gt[i].w};
;       unsigned ow[4];
; #pragma unroll
;       for (int e = 0; e < 4; ++e) {
;         float y0 = bflo(uw[e]) * mm[2 * e] * silu_f(bflo(gw[e]));
;         float y1 = bfhi(uw[e]) * mm[2 * e + 1] * silu_f(bfhi(gw[e]));
;         ow[e] = pack2(y0, y1);
;       }
;       *reinterpret_cast<uint4*>(Y + (t0 + t) * YW + g * 128 + c) = make_uint4(ow[0], ow[1], ow[2], ow[3]);
	v_lshlrev_b32_e32 v63, 16, v9
	s_waitcnt vmcnt(0)
	v_lshlrev_b32_e32 v25, 16, v56
	v_mul_f32_e32 v12, 0xbfb8aa3b, v25
	v_and_b32_e32 v35, 0xffff0000, v56
	v_lshlrev_b32_e32 v21, 16, v57
	v_exp_f32_e32 v60, v12
	v_mul_f32_e32 v12, 0xbfb8aa3b, v35
	v_exp_f32_e32 v56, v12
	v_mul_f32_e32 v12, 0xbfb8aa3b, v21
	v_exp_f32_e32 v61, v12
	v_and_b32_e32 v29, 0xffff0000, v57
	ds_read_b128 v[12:15], v16
	ds_read_b128 v[16:19], v16 offset:16
	v_lshlrev_b32_e32 v62, 16, v8
	v_pk_add_f32 v[60:61], v[60:61], 1.0 op_sel_hi:[1,0]
	v_and_b32_e32 v9, 0xffff0000, v9
	s_waitcnt lgkmcnt(1)
	v_mov_b32_e32 v64, v12
	v_mov_b32_e32 v65, v14
	v_pk_mul_f32 v[62:63], v[64:65], v[62:63]
	v_rcp_f32_e32 v61, v61
	s_nop 0
	v_mul_f32_e32 v61, v21, v61
	v_and_b32_e32 v8, 0xffff0000, v8
	v_mul_f32_e32 v14, 0xbfb8aa3b, v29
	v_exp_f32_e32 v57, v14
	v_rcp_f32_e32 v60, v60
	s_nop 0
	v_mul_f32_e32 v60, v25, v60
	v_mov_b32_e32 v14, v13
	v_pk_mul_f32 v[8:9], v[14:15], v[8:9]
	v_pk_add_f32 v[56:57], v[56:57], 1.0 op_sel_hi:[1,0]
	v_pk_mul_f32 v[60:61], v[60:61], v[62:63]
	v_lshlrev_b32_e32 v63, 16, v11
	v_lshlrev_b32_e32 v62, 16, v10
	v_and_b32_e32 v11, 0xffff0000, v11
	v_rcp_f32_e32 v13, v57
	s_nop 0
	v_mul_f32_e32 v13, v29, v13
	v_rcp_f32_e32 v12, v56
	s_nop 0
	v_mul_f32_e32 v12, v35, v12
	v_pk_mul_f32 v[8:9], v[12:13], v[8:9]
	v_cvt_pk_bf16_f32 v9, 0, v9
	v_cvt_pk_bf16_f32 v8, 0, v8
	v_cvt_pk_bf16_f32 v13, 0, v60
	v_cvt_pk_bf16_f32 v12, 0, v61
	v_and_b32_e32 v9, 0xffff0000, v9
	v_and_b32_e32 v8, 0xffff0000, v8
	v_lshlrev_b32_e32 v21, 16, v59
	v_lshlrev_b32_e32 v25, 16, v58
	v_or_b32_sdwa v9, v9, v12 dst_sel:DWORD dst_unused:UNUSED_PAD src0_sel:DWORD src1_sel:WORD_1
	v_or_b32_sdwa v8, v8, v13 dst_sel:DWORD dst_unused:UNUSED_PAD src0_sel:DWORD src1_sel:WORD_1
	v_mul_f32_e32 v12, 0xbfb8aa3b, v25
	v_mul_f32_e32 v13, 0xbfb8aa3b, v21
	v_exp_f32_e32 v12, v12
	v_exp_f32_e32 v13, v13
	v_and_b32_e32 v35, 0xffff0000, v58
	v_mul_f32_e32 v14, 0xbfb8aa3b, v35
	v_and_b32_e32 v29, 0xffff0000, v59
	v_exp_f32_e32 v60, v14
	v_pk_add_f32 v[64:65], v[12:13], 1.0 op_sel_hi:[1,0]
	global_load_dwordx4 v[12:15], v[22:23], off
	global_load_dwordx4 v[56:59], v[22:23], off offset:2048
	s_waitcnt lgkmcnt(0)
	v_mov_b32_e32 v22, v16
	v_mov_b32_e32 v23, v18
	v_pk_mul_f32 v[22:23], v[22:23], v[62:63]
	v_rcp_f32_e32 v63, v65
	s_nop 0
	v_mul_f32_e32 v63, v21, v63
	v_and_b32_e32 v10, 0xffff0000, v10
	v_mul_f32_e32 v18, 0xbfb8aa3b, v29
	v_exp_f32_e32 v61, v18
	v_rcp_f32_e32 v62, v64
	s_nop 0
	v_mul_f32_e32 v62, v25, v62
	v_mov_b32_e32 v18, v17
	v_pk_mul_f32 v[10:11], v[18:19], v[10:11]
	v_pk_add_f32 v[60:61], v[60:61], 1.0 op_sel_hi:[1,0]
	v_pk_mul_f32 v[22:23], v[62:63], v[22:23]
	s_waitcnt vmcnt(1)
	v_lshlrev_b32_e32 v63, 16, v13
	v_rcp_f32_e32 v17, v61
	s_nop 0
	v_mul_f32_e32 v17, v29, v17
	v_rcp_f32_e32 v16, v60
	s_nop 0
	v_mul_f32_e32 v16, v35, v16
	v_pk_mul_f32 v[10:11], v[16:17], v[10:11]
	v_cvt_pk_bf16_f32 v11, 0, v11
	v_cvt_pk_bf16_f32 v16, 0, v23
	v_and_b32_e32 v11, 0xffff0000, v11
	s_waitcnt vmcnt(0)
	v_lshlrev_b32_e32 v29, 16, v56
	v_or_b32_sdwa v11, v11, v16 dst_sel:DWORD dst_unused:UNUSED_PAD src0_sel:DWORD src1_sel:WORD_1
	v_mul_f32_e32 v16, 0xbfb8aa3b, v29
	v_and_b32_e32 v55, 0xffff0000, v56
	v_lshlrev_b32_e32 v25, 16, v57
	v_exp_f32_e32 v60, v16
	v_mul_f32_e32 v16, 0xbfb8aa3b, v55
	v_exp_f32_e32 v56, v16
	v_mul_f32_e32 v16, 0xbfb8aa3b, v25
	v_exp_f32_e32 v61, v16
	v_cvt_pk_bf16_f32 v10, 0, v10
	v_pk_add_f32 v[60:61], v[60:61], 1.0 op_sel_hi:[1,0]
	v_cvt_pk_bf16_f32 v17, 0, v22
	v_and_b32_e32 v10, 0xffff0000, v10
	v_and_b32_e32 v35, 0xffff0000, v57
	v_or_b32_sdwa v10, v10, v17 dst_sel:DWORD dst_unused:UNUSED_PAD src0_sel:DWORD src1_sel:WORD_1
	ds_read_b128 v[16:19], v20
	ds_read_b128 v[20:23], v20 offset:16
	v_lshlrev_b32_e32 v62, 16, v12
	v_and_b32_e32 v13, 0xffff0000, v13
	s_waitcnt lgkmcnt(1)
	v_mov_b32_e32 v64, v16
	v_mov_b32_e32 v65, v18
	v_pk_mul_f32 v[62:63], v[64:65], v[62:63]
	v_rcp_f32_e32 v61, v61
	s_nop 0
	v_mul_f32_e32 v61, v25, v61
	v_and_b32_e32 v12, 0xffff0000, v12
	v_mul_f32_e32 v18, 0xbfb8aa3b, v35
	v_exp_f32_e32 v57, v18
	v_rcp_f32_e32 v60, v60
	s_nop 0
	v_mul_f32_e32 v60, v29, v60
	v_mov_b32_e32 v18, v17
	v_pk_mul_f32 v[12:13], v[18:19], v[12:13]
	v_pk_add_f32 v[56:57], v[56:57], 1.0 op_sel_hi:[1,0]
	v_pk_mul_f32 v[60:61], v[60:61], v[62:63]
	v_lshlrev_b32_e32 v63, 16, v15
	v_lshlrev_b32_e32 v62, 16, v14
	v_and_b32_e32 v15, 0xffff0000, v15
	v_rcp_f32_e32 v17, v57
	s_nop 0
	v_mul_f32_e32 v17, v35, v17
	v_rcp_f32_e32 v16, v56
	s_nop 0
	v_mul_f32_e32 v16, v55, v16
	v_pk_mul_f32 v[12:13], v[16:17], v[12:13]
	v_cvt_pk_bf16_f32 v13, 0, v13
	v_cvt_pk_bf16_f32 v12, 0, v12
	v_cvt_pk_bf16_f32 v17, 0, v60
	v_cvt_pk_bf16_f32 v16, 0, v61
	v_and_b32_e32 v13, 0xffff0000, v13
	v_and_b32_e32 v12, 0xffff0000, v12
	v_lshlrev_b32_e32 v25, 16, v59
	v_lshlrev_b32_e32 v29, 16, v58
	v_or_b32_sdwa v13, v13, v16 dst_sel:DWORD dst_unused:UNUSED_PAD src0_sel:DWORD src1_sel:WORD_1
	v_or_b32_sdwa v12, v12, v17 dst_sel:DWORD dst_unused:UNUSED_PAD src0_sel:DWORD src1_sel:WORD_1
	v_mul_f32_e32 v16, 0xbfb8aa3b, v29
	v_mul_f32_e32 v17, 0xbfb8aa3b, v25
	v_exp_f32_e32 v16, v16
	v_exp_f32_e32 v17, v17
	v_and_b32_e32 v55, 0xffff0000, v58
	v_mul_f32_e32 v18, 0xbfb8aa3b, v55
	v_and_b32_e32 v35, 0xffff0000, v59
	v_exp_f32_e32 v60, v18
	v_pk_add_f32 v[64:65], v[16:17], 1.0 op_sel_hi:[1,0]
	global_load_dwordx4 v[16:19], v[26:27], off
	global_load_dwordx4 v[56:59], v[26:27], off offset:2048
	s_waitcnt lgkmcnt(0)
; __device__ __forceinline__ unsigned pack2(float a, float b) { return (unsigned)f2bf(a) | ((unsigned)f2bf(b) << 16); }
; __device__ __forceinline__ float bflo(unsigned w) { return __uint_as_float(w << 16); }
; __device__ __forceinline__ float bfhi(unsigned w) { return __uint_as_float(w & 0xffff0000u); }
; __device__ __forceinline__ float silu_f(float g) { return g / (1.f + __expf(-g)); }
; __device__ void gmlp_item(const Params& p, int layer, int b, int n, int g, char* smem) {
;     ...
; #pragma unroll
;     for (int i = 0; i < 8; ++i) {
;       int q = tid + 256 * i, t = q >> 4, c = (q & 15) * 8;
;       float4 m0 = *reinterpret_cast<const float4*>(Tf + t * 132 + c);
;       float4 m1 = *reinterpret_cast<const float4*>(Tf + t * 132 + c + 4);
;       float mm[8] = {m0.x, m0.y, m0.z, m0.w, m1.x, m1.y, m1.z, m1.w};
;       unsigned uw[4] = {uu[i].x, uu[i].y, uu[i].z, uu[i].w};
;       unsigned gw[4] = {gt[i].x, gt[i].y, gt[i].z, gt[i].w};
;       unsigned ow[4];
; #pragma unroll
;       for (int e = 0; e < 4; ++e) {
;         float y0 = bflo(uw[e]) * mm[2 * e] * silu_f(bflo(gw[e]));
;         float y1 = bfhi(uw[e]) * mm[2 * e + 1] * silu_f(bfhi(gw[e]));
;         ow[e] = pack2(y0, y1);
;       }
;       *reinterpret_cast<uint4*>(Y + (t0 + t) * YW + g * 128 + c) = make_uint4(ow[0], ow[1], ow[2], ow[3]);
	v_mov_b32_e32 v26, v20
	v_mov_b32_e32 v27, v22
	v_pk_mul_f32 v[26:27], v[26:27], v[62:63]
	v_rcp_f32_e32 v63, v65
	s_nop 0
	v_mul_f32_e32 v63, v25, v63
	v_and_b32_e32 v14, 0xffff0000, v14
	v_mul_f32_e32 v22, 0xbfb8aa3b, v35
	v_exp_f32_e32 v61, v22
	v_rcp_f32_e32 v62, v64
	s_nop 0
	v_mul_f32_e32 v62, v29, v62
	v_mov_b32_e32 v22, v21
	v_pk_mul_f32 v[14:15], v[22:23], v[14:15]
	v_pk_add_f32 v[60:61], v[60:61], 1.0 op_sel_hi:[1,0]
	v_pk_mul_f32 v[26:27], v[62:63], v[26:27]
	s_waitcnt vmcnt(1)
	v_lshlrev_b32_e32 v63, 16, v17
	v_rcp_f32_e32 v21, v61
	s_nop 0
	v_mul_f32_e32 v21, v35, v21
	v_rcp_f32_e32 v20, v60
	s_nop 0
	v_mul_f32_e32 v20, v55, v20
	v_pk_mul_f32 v[14:15], v[20:21], v[14:15]
	v_cvt_pk_bf16_f32 v15, 0, v15
	v_cvt_pk_bf16_f32 v20, 0, v27
	v_and_b32_e32 v15, 0xffff0000, v15
	s_waitcnt vmcnt(0)
	v_lshlrev_b32_e32 v35, 16, v56
	v_or_b32_sdwa v15, v15, v20 dst_sel:DWORD dst_unused:UNUSED_PAD src0_sel:DWORD src1_sel:WORD_1
	v_mul_f32_e32 v20, 0xbfb8aa3b, v35
	v_and_b32_e32 v66, 0xffff0000, v56
	v_lshlrev_b32_e32 v29, 16, v57
	v_exp_f32_e32 v60, v20
	v_mul_f32_e32 v20, 0xbfb8aa3b, v66
	v_exp_f32_e32 v56, v20
	v_mul_f32_e32 v20, 0xbfb8aa3b, v29
	v_exp_f32_e32 v61, v20
	v_cvt_pk_bf16_f32 v14, 0, v14
	v_pk_add_f32 v[60:61], v[60:61], 1.0 op_sel_hi:[1,0]
	v_cvt_pk_bf16_f32 v21, 0, v26
	v_and_b32_e32 v14, 0xffff0000, v14
	v_and_b32_e32 v55, 0xffff0000, v57
	v_or_b32_sdwa v14, v14, v21 dst_sel:DWORD dst_unused:UNUSED_PAD src0_sel:DWORD src1_sel:WORD_1
	ds_read_b128 v[20:23], v24
	ds_read_b128 v[24:27], v24 offset:16
	v_lshlrev_b32_e32 v62, 16, v16
	v_and_b32_e32 v17, 0xffff0000, v17
	s_waitcnt lgkmcnt(1)
	v_mov_b32_e32 v64, v20
	v_mov_b32_e32 v65, v22
	v_pk_mul_f32 v[62:63], v[64:65], v[62:63]
	v_rcp_f32_e32 v61, v61
	s_nop 0
	v_mul_f32_e32 v61, v29, v61
	v_and_b32_e32 v16, 0xffff0000, v16
	v_mul_f32_e32 v22, 0xbfb8aa3b, v55
	v_exp_f32_e32 v57, v22
	v_rcp_f32_e32 v60, v60
	s_nop 0
	v_mul_f32_e32 v60, v35, v60
	v_mov_b32_e32 v22, v21
	v_pk_mul_f32 v[16:17], v[22:23], v[16:17]
	v_pk_add_f32 v[56:57], v[56:57], 1.0 op_sel_hi:[1,0]
	v_pk_mul_f32 v[60:61], v[60:61], v[62:63]
	v_lshlrev_b32_e32 v63, 16, v19
	v_lshlrev_b32_e32 v62, 16, v18
	v_and_b32_e32 v19, 0xffff0000, v19
	v_rcp_f32_e32 v21, v57
	s_nop 0
	v_mul_f32_e32 v21, v55, v21
	v_rcp_f32_e32 v20, v56
	s_nop 0
	v_mul_f32_e32 v20, v66, v20
	v_pk_mul_f32 v[16:17], v[20:21], v[16:17]
	v_cvt_pk_bf16_f32 v17, 0, v17
	v_cvt_pk_bf16_f32 v16, 0, v16
	v_cvt_pk_bf16_f32 v21, 0, v60
	v_cvt_pk_bf16_f32 v20, 0, v61
	v_and_b32_e32 v17, 0xffff0000, v17
	v_and_b32_e32 v16, 0xffff0000, v16
	v_lshlrev_b32_e32 v29, 16, v59
	v_lshlrev_b32_e32 v35, 16, v58
	v_or_b32_sdwa v17, v17, v20 dst_sel:DWORD dst_unused:UNUSED_PAD src0_sel:DWORD src1_sel:WORD_1
	v_or_b32_sdwa v16, v16, v21 dst_sel:DWORD dst_unused:UNUSED_PAD src0_sel:DWORD src1_sel:WORD_1
	v_mul_f32_e32 v20, 0xbfb8aa3b, v35
	v_mul_f32_e32 v21, 0xbfb8aa3b, v29
	v_exp_f32_e32 v20, v20
	v_exp_f32_e32 v21, v21
	v_and_b32_e32 v66, 0xffff0000, v58
	v_mul_f32_e32 v22, 0xbfb8aa3b, v66
	v_and_b32_e32 v55, 0xffff0000, v59
	v_exp_f32_e32 v60, v22
	v_pk_add_f32 v[64:65], v[20:21], 1.0 op_sel_hi:[1,0]
	global_load_dwordx4 v[20:23], v[30:31], off
	global_load_dwordx4 v[56:59], v[30:31], off offset:2048
	s_waitcnt lgkmcnt(0)
	v_mov_b32_e32 v30, v24
	v_mov_b32_e32 v31, v26
	v_pk_mul_f32 v[30:31], v[30:31], v[62:63]
	v_rcp_f32_e32 v63, v65
	s_nop 0
	v_mul_f32_e32 v63, v29, v63
	v_and_b32_e32 v18, 0xffff0000, v18
	v_mul_f32_e32 v26, 0xbfb8aa3b, v55
	v_exp_f32_e32 v61, v26
	v_rcp_f32_e32 v62, v64
	s_nop 0
	v_mul_f32_e32 v62, v35, v62
	v_mov_b32_e32 v26, v25
	v_pk_mul_f32 v[18:19], v[26:27], v[18:19]
	v_pk_add_f32 v[60:61], v[60:61], 1.0 op_sel_hi:[1,0]
	v_pk_mul_f32 v[30:31], v[62:63], v[30:31]
	s_waitcnt vmcnt(1)
	v_lshlrev_b32_e32 v63, 16, v21
	v_rcp_f32_e32 v25, v61
	s_nop 0
	v_mul_f32_e32 v25, v55, v25
	v_rcp_f32_e32 v24, v60
	s_nop 0
	v_mul_f32_e32 v24, v66, v24
	v_pk_mul_f32 v[18:19], v[24:25], v[18:19]
	v_cvt_pk_bf16_f32 v19, 0, v19
	v_cvt_pk_bf16_f32 v24, 0, v31
	v_and_b32_e32 v19, 0xffff0000, v19
	s_waitcnt vmcnt(0)
	v_lshlrev_b32_e32 v55, 16, v56
	v_or_b32_sdwa v19, v19, v24 dst_sel:DWORD dst_unused:UNUSED_PAD src0_sel:DWORD src1_sel:WORD_1
	v_mul_f32_e32 v24, 0xbfb8aa3b, v55
	v_and_b32_e32 v67, 0xffff0000, v56
	v_lshlrev_b32_e32 v35, 16, v57
	v_exp_f32_e32 v60, v24
	v_mul_f32_e32 v24, 0xbfb8aa3b, v67
	v_exp_f32_e32 v56, v24
	v_mul_f32_e32 v24, 0xbfb8aa3b, v35
	v_exp_f32_e32 v61, v24
	v_cvt_pk_bf16_f32 v18, 0, v18
	v_pk_add_f32 v[60:61], v[60:61], 1.0 op_sel_hi:[1,0]
	v_cvt_pk_bf16_f32 v25, 0, v30
	v_and_b32_e32 v18, 0xffff0000, v18
	v_and_b32_e32 v66, 0xffff0000, v57
	v_or_b32_sdwa v18, v18, v25 dst_sel:DWORD dst_unused:UNUSED_PAD src0_sel:DWORD src1_sel:WORD_1
	ds_read_b128 v[24:27], v28
	ds_read_b128 v[28:31], v28 offset:16
	v_lshlrev_b32_e32 v62, 16, v20
	v_and_b32_e32 v21, 0xffff0000, v21
	s_waitcnt lgkmcnt(1)
; __device__ __forceinline__ unsigned pack2(float a, float b) { return (unsigned)f2bf(a) | ((unsigned)f2bf(b) << 16); }
; __device__ __forceinline__ float bflo(unsigned w) { return __uint_as_float(w << 16); }
; __device__ __forceinline__ float bfhi(unsigned w) { return __uint_as_float(w & 0xffff0000u); }
; __device__ __forceinline__ float silu_f(float g) { return g / (1.f + __expf(-g)); }
; __device__ void gmlp_item(const Params& p, int layer, int b, int n, int g, char* smem) {
;     ...
; #pragma unroll
;     for (int i = 0; i < 8; ++i) {
;       int q = tid + 256 * i, t = q >> 4, c = (q & 15) * 8;
;       float4 m0 = *reinterpret_cast<const float4*>(Tf + t * 132 + c);
;       float4 m1 = *reinterpret_cast<const float4*>(Tf + t * 132 + c + 4);
;       float mm[8] = {m0.x, m0.y, m0.z, m0.w, m1.x, m1.y, m1.z, m1.w};
;       unsigned uw[4] = {uu[i].x, uu[i].y, uu[i].z, uu[i].w};
;       unsigned gw[4] = {gt[i].x, gt[i].y, gt[i].z, gt[i].w};
;       unsigned ow[4];
; #pragma unroll
;       for (int e = 0; e < 4; ++e) {
;         float y0 = bflo(uw[e]) * mm[2 * e] * silu_f(bflo(gw[e]));
;         float y1 = bfhi(uw[e]) * mm[2 * e + 1] * silu_f(bfhi(gw[e]));
;         ow[e] = pack2(y0, y1);
;       }
;       *reinterpret_cast<uint4*>(Y + (t0 + t) * YW + g * 128 + c) = make_uint4(ow[0], ow[1], ow[2], ow[3]);
;     }
	v_mov_b32_e32 v64, v24
	v_mov_b32_e32 v65, v26
	v_pk_mul_f32 v[62:63], v[64:65], v[62:63]
	v_rcp_f32_e32 v61, v61
	s_nop 0
	v_mul_f32_e32 v61, v35, v61
	v_and_b32_e32 v20, 0xffff0000, v20
	v_mul_f32_e32 v26, 0xbfb8aa3b, v66
	v_exp_f32_e32 v57, v26
	v_rcp_f32_e32 v60, v60
	s_nop 0
	v_mul_f32_e32 v60, v55, v60
	v_mov_b32_e32 v26, v25
	v_pk_mul_f32 v[20:21], v[26:27], v[20:21]
	v_pk_add_f32 v[56:57], v[56:57], 1.0 op_sel_hi:[1,0]
	v_pk_mul_f32 v[60:61], v[60:61], v[62:63]
	v_lshlrev_b32_e32 v63, 16, v23
	v_lshlrev_b32_e32 v62, 16, v22
	v_and_b32_e32 v23, 0xffff0000, v23
	v_rcp_f32_e32 v25, v57
	s_nop 0
	v_mul_f32_e32 v25, v66, v25
	v_rcp_f32_e32 v24, v56
	s_nop 0
	v_mul_f32_e32 v24, v67, v24
	v_pk_mul_f32 v[20:21], v[24:25], v[20:21]
	v_cvt_pk_bf16_f32 v21, 0, v21
	v_cvt_pk_bf16_f32 v20, 0, v20
	v_cvt_pk_bf16_f32 v25, 0, v60
	v_cvt_pk_bf16_f32 v24, 0, v61
	v_and_b32_e32 v21, 0xffff0000, v21
	v_and_b32_e32 v20, 0xffff0000, v20
	v_lshlrev_b32_e32 v35, 16, v59
	v_lshlrev_b32_e32 v55, 16, v58
	v_or_b32_sdwa v21, v21, v24 dst_sel:DWORD dst_unused:UNUSED_PAD src0_sel:DWORD src1_sel:WORD_1
	v_or_b32_sdwa v20, v20, v25 dst_sel:DWORD dst_unused:UNUSED_PAD src0_sel:DWORD src1_sel:WORD_1
	v_mul_f32_e32 v24, 0xbfb8aa3b, v55
	v_mul_f32_e32 v25, 0xbfb8aa3b, v35
	v_exp_f32_e32 v24, v24
	v_exp_f32_e32 v25, v25
	v_and_b32_e32 v67, 0xffff0000, v58
	v_mul_f32_e32 v26, 0xbfb8aa3b, v67
	v_and_b32_e32 v66, 0xffff0000, v59
	v_exp_f32_e32 v60, v26
	v_pk_add_f32 v[64:65], v[24:25], 1.0 op_sel_hi:[1,0]
	global_load_dwordx4 v[24:27], v[32:33], off
	global_load_dwordx4 v[56:59], v[32:33], off offset:2048
	s_waitcnt lgkmcnt(0)
	v_mov_b32_e32 v32, v28
	v_mov_b32_e32 v33, v30
	v_pk_mul_f32 v[32:33], v[32:33], v[62:63]
	v_rcp_f32_e32 v63, v65
	s_nop 0
	v_mul_f32_e32 v63, v35, v63
	v_and_b32_e32 v22, 0xffff0000, v22
	v_mul_f32_e32 v30, 0xbfb8aa3b, v66
	v_exp_f32_e32 v61, v30
	v_rcp_f32_e32 v62, v64
	s_nop 0
	v_mul_f32_e32 v62, v55, v62
	v_mov_b32_e32 v30, v29
	v_pk_mul_f32 v[22:23], v[30:31], v[22:23]
	v_pk_add_f32 v[60:61], v[60:61], 1.0 op_sel_hi:[1,0]
	v_pk_mul_f32 v[32:33], v[62:63], v[32:33]
	s_waitcnt vmcnt(1)
	v_lshlrev_b32_e32 v63, 16, v25
	v_rcp_f32_e32 v29, v61
	s_nop 0
	v_mul_f32_e32 v29, v66, v29
	v_rcp_f32_e32 v28, v60
	s_nop 0
	v_mul_f32_e32 v28, v67, v28
	v_pk_mul_f32 v[22:23], v[28:29], v[22:23]
	v_cvt_pk_bf16_f32 v23, 0, v23
	v_cvt_pk_bf16_f32 v28, 0, v33
	v_and_b32_e32 v23, 0xffff0000, v23
	s_waitcnt vmcnt(0)
	v_lshlrev_b32_e32 v66, 16, v56
	v_or_b32_sdwa v23, v23, v28 dst_sel:DWORD dst_unused:UNUSED_PAD src0_sel:DWORD src1_sel:WORD_1
	v_mul_f32_e32 v28, 0xbfb8aa3b, v66
	v_and_b32_e32 v68, 0xffff0000, v56
	v_lshlrev_b32_e32 v55, 16, v57
	v_exp_f32_e32 v60, v28
	v_mul_f32_e32 v28, 0xbfb8aa3b, v68
	v_exp_f32_e32 v56, v28
	v_mul_f32_e32 v28, 0xbfb8aa3b, v55
	v_exp_f32_e32 v61, v28
	v_cvt_pk_bf16_f32 v22, 0, v22
	v_pk_add_f32 v[60:61], v[60:61], 1.0 op_sel_hi:[1,0]
	v_cvt_pk_bf16_f32 v29, 0, v32
	v_and_b32_e32 v22, 0xffff0000, v22
	v_and_b32_e32 v67, 0xffff0000, v57
	v_or_b32_sdwa v22, v22, v29 dst_sel:DWORD dst_unused:UNUSED_PAD src0_sel:DWORD src1_sel:WORD_1
	ds_read_b128 v[28:31], v34
	ds_read_b128 v[32:35], v34 offset:16
	v_lshlrev_b32_e32 v62, 16, v24
	v_and_b32_e32 v25, 0xffff0000, v25
	s_waitcnt lgkmcnt(1)
	v_mov_b32_e32 v64, v28
	v_mov_b32_e32 v65, v30
	v_pk_mul_f32 v[62:63], v[64:65], v[62:63]
	v_rcp_f32_e32 v61, v61
	s_nop 0
	v_mul_f32_e32 v61, v55, v61
	v_and_b32_e32 v24, 0xffff0000, v24
	v_mul_f32_e32 v30, 0xbfb8aa3b, v67
	v_exp_f32_e32 v57, v30
	v_rcp_f32_e32 v60, v60
	s_nop 0
	v_mul_f32_e32 v60, v66, v60
	v_mov_b32_e32 v30, v29
	v_pk_mul_f32 v[24:25], v[30:31], v[24:25]
	v_pk_add_f32 v[56:57], v[56:57], 1.0 op_sel_hi:[1,0]
	v_pk_mul_f32 v[60:61], v[60:61], v[62:63]
	v_lshlrev_b32_e32 v66, 16, v58
	v_lshlrev_b32_e32 v63, 16, v27
	v_and_b32_e32 v27, 0xffff0000, v27
	v_rcp_f32_e32 v29, v57
	s_nop 0
	v_mul_f32_e32 v29, v67, v29
	v_rcp_f32_e32 v28, v56
	s_nop 0
	v_mul_f32_e32 v28, v68, v28
	v_pk_mul_f32 v[24:25], v[28:29], v[24:25]
	v_cvt_pk_bf16_f32 v25, 0, v25
	v_cvt_pk_bf16_f32 v24, 0, v24
	v_cvt_pk_bf16_f32 v29, 0, v60
	v_cvt_pk_bf16_f32 v28, 0, v61
	v_and_b32_e32 v25, 0xffff0000, v25
	v_and_b32_e32 v24, 0xffff0000, v24
	v_lshlrev_b32_e32 v55, 16, v59
	v_or_b32_sdwa v25, v25, v28 dst_sel:DWORD dst_unused:UNUSED_PAD src0_sel:DWORD src1_sel:WORD_1
	v_or_b32_sdwa v24, v24, v29 dst_sel:DWORD dst_unused:UNUSED_PAD src0_sel:DWORD src1_sel:WORD_1
	v_mul_f32_e32 v28, 0xbfb8aa3b, v66
	v_mul_f32_e32 v29, 0xbfb8aa3b, v55
	v_exp_f32_e32 v28, v28
	v_exp_f32_e32 v29, v29
	v_and_b32_e32 v68, 0xffff0000, v58
	v_mul_f32_e32 v30, 0xbfb8aa3b, v68
	v_and_b32_e32 v67, 0xffff0000, v59
	v_exp_f32_e32 v60, v30
	v_pk_add_f32 v[64:65], v[28:29], 1.0 op_sel_hi:[1,0]
	global_load_dwordx4 v[28:31], v[52:53], off
	global_load_dwordx4 v[56:59], v[52:53], off offset:2048
	s_waitcnt lgkmcnt(0)
; __device__ __forceinline__ unsigned pack2(float a, float b) { return (unsigned)f2bf(a) | ((unsigned)f2bf(b) << 16); }
; __device__ __forceinline__ float bflo(unsigned w) { return __uint_as_float(w << 16); }
; __device__ __forceinline__ float bfhi(unsigned w) { return __uint_as_float(w & 0xffff0000u); }
; __device__ __forceinline__ float silu_f(float g) { return g / (1.f + __expf(-g)); }
; __device__ void gmlp_item(const Params& p, int layer, int b, int n, int g, char* smem) {
;     ...
; #pragma unroll
;     for (int i = 0; i < 8; ++i) {
;       int q = tid + 256 * i, t = q >> 4, c = (q & 15) * 8;
;       float4 m0 = *reinterpret_cast<const float4*>(Tf + t * 132 + c);
;       float4 m1 = *reinterpret_cast<const float4*>(Tf + t * 132 + c + 4);
;       float mm[8] = {m0.x, m0.y, m0.z, m0.w, m1.x, m1.y, m1.z, m1.w};
;       unsigned uw[4] = {uu[i].x, uu[i].y, uu[i].z, uu[i].w};
;       unsigned gw[4] = {gt[i].x, gt[i].y, gt[i].z, gt[i].w};
;       unsigned ow[4];
; #pragma unroll
;       for (int e = 0; e < 4; ++e) {
;         float y0 = bflo(uw[e]) * mm[2 * e] * silu_f(bflo(gw[e]));
;         float y1 = bfhi(uw[e]) * mm[2 * e + 1] * silu_f(bfhi(gw[e]));
;         ow[e] = pack2(y0, y1);
;       }
;       *reinterpret_cast<uint4*>(Y + (t0 + t) * YW + g * 128 + c) = make_uint4(ow[0], ow[1], ow[2], ow[3]);
;     }
	v_mov_b32_e32 v52, v32
	v_lshlrev_b32_e32 v62, 16, v26
	v_mov_b32_e32 v53, v34
	v_pk_mul_f32 v[52:53], v[52:53], v[62:63]
	v_rcp_f32_e32 v63, v65
	s_nop 0
	v_mul_f32_e32 v63, v55, v63
	v_and_b32_e32 v26, 0xffff0000, v26
	v_mul_f32_e32 v34, 0xbfb8aa3b, v67
	v_exp_f32_e32 v61, v34
	v_rcp_f32_e32 v62, v64
	s_nop 0
	v_mul_f32_e32 v62, v66, v62
	v_mov_b32_e32 v34, v33
	v_pk_mul_f32 v[26:27], v[34:35], v[26:27]
	v_pk_add_f32 v[60:61], v[60:61], 1.0 op_sel_hi:[1,0]
	v_pk_mul_f32 v[52:53], v[62:63], v[52:53]
	s_waitcnt vmcnt(1)
	v_lshlrev_b32_e32 v63, 16, v29
	v_rcp_f32_e32 v33, v61
	s_nop 0
	v_mul_f32_e32 v33, v67, v33
	v_rcp_f32_e32 v32, v60
	s_nop 0
	v_mul_f32_e32 v32, v68, v32
	v_pk_mul_f32 v[26:27], v[32:33], v[26:27]
	v_cvt_pk_bf16_f32 v27, 0, v27
	v_cvt_pk_bf16_f32 v32, 0, v53
	v_and_b32_e32 v27, 0xffff0000, v27
	s_waitcnt vmcnt(0)
	v_lshlrev_b32_e32 v67, 16, v56
	v_or_b32_sdwa v27, v27, v32 dst_sel:DWORD dst_unused:UNUSED_PAD src0_sel:DWORD src1_sel:WORD_1
	v_mul_f32_e32 v32, 0xbfb8aa3b, v67
	v_and_b32_e32 v69, 0xffff0000, v56
	v_lshlrev_b32_e32 v66, 16, v57
	v_exp_f32_e32 v60, v32
	v_mul_f32_e32 v32, 0xbfb8aa3b, v69
	v_exp_f32_e32 v56, v32
	v_mul_f32_e32 v32, 0xbfb8aa3b, v66
	v_exp_f32_e32 v61, v32
	v_cvt_pk_bf16_f32 v26, 0, v26
	v_pk_add_f32 v[60:61], v[60:61], 1.0 op_sel_hi:[1,0]
	v_cvt_pk_bf16_f32 v33, 0, v52
	v_and_b32_e32 v26, 0xffff0000, v26
	v_and_b32_e32 v68, 0xffff0000, v57
	v_or_b32_sdwa v26, v26, v33 dst_sel:DWORD dst_unused:UNUSED_PAD src0_sel:DWORD src1_sel:WORD_1
	ds_read_b128 v[32:35], v54
	ds_read_b128 v[52:55], v54 offset:16
	v_lshlrev_b32_e32 v62, 16, v28
	v_and_b32_e32 v29, 0xffff0000, v29
	s_waitcnt lgkmcnt(1)
	v_mov_b32_e32 v64, v32
	v_mov_b32_e32 v65, v34
	v_pk_mul_f32 v[62:63], v[64:65], v[62:63]
	v_rcp_f32_e32 v61, v61
	s_nop 0
	v_mul_f32_e32 v61, v66, v61
	v_and_b32_e32 v28, 0xffff0000, v28
	v_mul_f32_e32 v34, 0xbfb8aa3b, v68
	v_exp_f32_e32 v57, v34
	v_rcp_f32_e32 v60, v60
	s_nop 0
	v_mul_f32_e32 v60, v67, v60
	v_pk_mul_f32 v[60:61], v[60:61], v[62:63]
	v_mov_b32_e32 v34, v33
	v_pk_add_f32 v[56:57], v[56:57], 1.0 op_sel_hi:[1,0]
	v_pk_mul_f32 v[28:29], v[34:35], v[28:29]
	s_nop 0
	v_rcp_f32_e32 v33, v57
	s_nop 0
	v_mul_f32_e32 v33, v68, v33
	v_rcp_f32_e32 v32, v56
	s_nop 0
	v_mul_f32_e32 v32, v69, v32
	v_pk_mul_f32 v[28:29], v[32:33], v[28:29]
	v_cvt_pk_bf16_f32 v29, 0, v29
	v_cvt_pk_bf16_f32 v28, 0, v28
	v_cvt_pk_bf16_f32 v33, 0, v60
	v_cvt_pk_bf16_f32 v32, 0, v61
	v_and_b32_e32 v29, 0xffff0000, v29
	v_and_b32_e32 v28, 0xffff0000, v28
	v_lshlrev_b32_e32 v35, 16, v59
	v_lshlrev_b32_e32 v60, 16, v58
	v_or_b32_sdwa v29, v29, v32 dst_sel:DWORD dst_unused:UNUSED_PAD src0_sel:DWORD src1_sel:WORD_1
	v_or_b32_sdwa v28, v28, v33 dst_sel:DWORD dst_unused:UNUSED_PAD src0_sel:DWORD src1_sel:WORD_1
	v_mul_f32_e32 v32, 0xbfb8aa3b, v60
	v_mul_f32_e32 v33, 0xbfb8aa3b, v35
	v_exp_f32_e32 v32, v32
	v_exp_f32_e32 v33, v33
	v_and_b32_e32 v62, 0xffff0000, v58
	s_waitcnt lgkmcnt(0)
	v_mov_b32_e32 v58, v52
	v_and_b32_e32 v61, 0xffff0000, v59
	v_pk_add_f32 v[32:33], v[32:33], 1.0 op_sel_hi:[1,0]
	v_lshlrev_b32_e32 v57, 16, v31
	v_lshlrev_b32_e32 v56, 16, v30
	v_mov_b32_e32 v59, v54
	v_pk_mul_f32 v[56:57], v[58:59], v[56:57]
	v_rcp_f32_e32 v33, v33
	s_nop 0
	v_mul_f32_e32 v33, v35, v33
	v_mul_f32_e32 v34, 0xbfb8aa3b, v62
	v_mul_f32_e32 v35, 0xbfb8aa3b, v61
	v_exp_f32_e32 v34, v34
	v_exp_f32_e32 v35, v35
	v_rcp_f32_e32 v32, v32
	s_nop 0
	v_mul_f32_e32 v32, v60, v32
	v_pk_mul_f32 v[32:33], v[32:33], v[56:57]
	v_mov_b32_e32 v54, v53
	v_pk_add_f32 v[34:35], v[34:35], 1.0 op_sel_hi:[1,0]
	v_and_b32_e32 v31, 0xffff0000, v31
	v_and_b32_e32 v30, 0xffff0000, v30
	v_pk_mul_f32 v[30:31], v[54:55], v[30:31]
	v_rcp_f32_e32 v35, v35
	s_nop 0
	v_mul_f32_e32 v35, v61, v35
	s_mov_b64 s[12:13], 0
	v_rcp_f32_e32 v34, v34
	s_nop 0
	v_mul_f32_e32 v34, v62, v34
	v_pk_mul_f32 v[30:31], v[34:35], v[30:31]
	v_cvt_pk_bf16_f32 v32, 0, v32
	v_cvt_pk_bf16_f32 v33, 0, v33
	v_cvt_pk_bf16_f32 v31, 0, v31
	v_cvt_pk_bf16_f32 v30, 0, v30
	v_and_b32_e32 v31, 0xffff0000, v31
	v_and_b32_e32 v30, 0xffff0000, v30
	v_or_b32_sdwa v31, v31, v33 dst_sel:DWORD dst_unused:UNUSED_PAD src0_sel:DWORD src1_sel:WORD_1
	v_or_b32_sdwa v30, v30, v32 dst_sel:DWORD dst_unused:UNUSED_PAD src0_sel:DWORD src1_sel:WORD_1
	global_store_dwordx4 v[50:51], v[28:31], off
	global_store_dwordx4 v[48:49], v[24:27], off
	global_store_dwordx4 v[46:47], v[20:23], off
	global_store_dwordx4 v[44:45], v[16:19], off
	global_store_dwordx4 v[42:43], v[12:15], off
	global_store_dwordx4 v[40:41], v[8:11], off
	global_store_dwordx4 v[38:39], v[4:7], off
	global_store_dwordx4 v[36:37], v[0:3], off
	s_barrier

; template <int DH, int MODE>
; __device__ void attn_item(const Params& p, int layer, int b, int blk, int head, char* smem) {
;     ...
;       if (MODE == 0) {
;         const int kjb = kj0 + half * 32;
;         float tmax = -1e30f;
; #pragma unroll
;         for (int c = 0; c < 8; ++c) {
;           float4 v = s4[c];
;           float e[4] = {v.x, v.y, v.z, v.w};
; #pragma unroll
;           for (int k = 0; k < 4; ++k) {
;             int kj = kjb + c * 4 + k;
;             bool valid = (kj > row) && (kj <= row + 128);
;             tmax = valid ? fmaxf(tmax, e[k]) : tmax;
;           }
.LBB0_808:
	s_or_b64 exec, exec, s[14:15]
	s_add_i32 s89, s89, 1
	s_min_i32 s14, s89, s87
	s_add_i32 s14, s14, s86
	s_lshl_b32 s14, s14, 6
	s_add_i32 s14, s14, s88
	s_ashr_i32 s15, s14, 31
	s_add_u32 s14, s14, s84
	s_addc_u32 s15, s15, 0
	s_waitcnt lgkmcnt(0)
	s_barrier
	ds_write_b16 v96, v48
	ds_write_b16_d16_hi v96, v48 offset:64
	ds_write_b16 v96, v49 offset:128
	ds_write_b16_d16_hi v96, v49 offset:192
	ds_write_b16 v96, v50 offset:256
	ds_write_b16_d16_hi v96, v50 offset:320
	ds_write_b16 v96, v51 offset:384
	ds_write_b16_d16_hi v96, v51 offset:448
	s_waitcnt vmcnt(0)
	ds_write_b16 v96, v52 offset:2048
	ds_write_b16_d16_hi v96, v52 offset:2112
	ds_write_b16 v96, v53 offset:2176
	ds_write_b16_d16_hi v96, v53 offset:2240
	ds_write_b16 v96, v54 offset:2304
	ds_write_b16_d16_hi v96, v54 offset:2368
	ds_write_b16 v96, v55 offset:2432
	ds_write_b16_d16_hi v96, v55 offset:2496
	v_lshl_add_u64 v[48:49], s[14:15], 0, v[66:67]
	v_mad_u64_u32 v[52:53], s[20:21], v48, s45, v[76:77]
	v_or_b32_e32 v48, s14, v72
	v_mad_i32_i24 v53, v49, s45, v53
	v_mad_u64_u32 v[54:55], s[20:21], v48, s45, v[78:79]
	v_add_co_u32_e32 v48, vcc, 0x4c000, v52
	v_mad_i32_i24 v55, s15, v160, v55
	s_nop 0
	v_addc_co_u32_e32 v49, vcc, 0, v53, vcc
	global_load_dwordx4 v[60:63], v[48:49], off
	s_nop 0
	global_load_dwordx4 v[48:51], v[54:55], off
	global_load_dwordx4 v[56:59], v[52:53], off
	s_nop 0
	global_load_dwordx4 v[52:55], v[54:55], off offset:64
	s_and_saveexec_b64 s[52:53], s[50:51]
	s_cbranch_execz .LBB0_830
	v_add_u32_e32 v82, 0x4004, v90
	ds_read2_b32 v[82:83], v82 offset1:1
	ds_read_b32 v102, v90 offset:16396
	v_or_b32_e32 v101, s16, v89
	v_cmp_gt_i32_e32 vcc, v101, v74
	v_cmp_le_i32_e64 s[14:15], v101, v80
	s_and_b64 s[16:17], vcc, s[14:15]
	v_mov_b32_e32 v103, 0xf149f2ca
	s_and_saveexec_b64 s[14:15], s[16:17]
	s_cbranch_execz .LBB0_811
	ds_read_b32 v103, v90 offset:16384
	s_waitcnt lgkmcnt(0)
	v_max_f32_e32 v103, 0xf149f2ca, v103

; __device__ __forceinline__ unsigned pack2(float a, float b) { return (unsigned)f2bf(a) | ((unsigned)f2bf(b) << 16); }
; __device__ __forceinline__ float bflo(unsigned w) { return __uint_as_float(w << 16); }
; __device__ __forceinline__ float bfhi(unsigned w) { return __uint_as_float(w & 0xffff0000u); }
; __device__ __forceinline__ float silu_f(float g) { return g / (1.f + __expf(-g)); }
; template <int DH, int MODE>
; __device__ void attn_item(const Params& p, int layer, int b, int blk, int head, char* smem) {
;     ...
;   if (MODE == 0 && half == 0) linv_s[row] = 1.f / l_run;
;   __syncthreads();
;   {
;     constexpr int OST = DH + 4;
;     constexpr int CPR = DH / 8;
;     constexpr int NCH = 128 * CPR / 256;
;     float* Of = reinterpret_cast<float*>(smem);
;     uint4 gt[NCH];
; #pragma unroll
;     for (int i = 0; i < NCH; ++i) {
;       int q = tid + 256 * i, r = q / CPR, c = (q % CPR) * 8;
;       gt[i] = *reinterpret_cast<const uint4*>(P + (tq0 + r) * NP + gcol + c);
;     }
;     float lis[2][4];
; #pragma unroll
;     for (int m = 0; m < 2; ++m)
; #pragma unroll
;       for (int j = 0; j < 4; ++j) lis[m][j] = (MODE == 0) ? linv_s[wid * 32 + m * 16 + fq * 4 + j] : 1.f;
;     if (MODE == 0) __syncthreads();
; #pragma unroll
;     for (int m = 0; m < 2; ++m)
; #pragma unroll
;       for (int j = 0; j < 4; ++j) {
;         int r = wid * 32 + m * 16 + fq * 4 + j;
; #pragma unroll
;         for (int n = 0; n < NDT; ++n) Of[r * OST + n * 16 + fr] = o[m][n][j] * lis[m][j];
;       }
;     __syncthreads();
; #pragma unroll
;     for (int i = 0; i < NCH; ++i) {
;       int q = tid + 256 * i, r = q / CPR, c = (q % CPR) * 8;
;       float4 m0 = *reinterpret_cast<const float4*>(Of + r * OST + c);
;       float4 m1 = *reinterpret_cast<const float4*>(Of + r * OST + c + 4);
;       float mm[8] = {m0.x, m0.y, m0.z, m0.w, m1.x, m1.y, m1.z, m1.w};
;       unsigned gw[4] = {gt[i].x, gt[i].y, gt[i].z, gt[i].w};
;       unsigned ow[4];
; #pragma unroll
;       for (int e = 0; e < 4; ++e)
;         ow[e] = pack2(mm[2 * e] * silu_f(bflo(gw[e])), mm[2 * e + 1] * silu_f(bfhi(gw[e])));
.LBB0_834:
	s_or_b64 exec, exec, s[14:15]
	v_lshl_add_u64 v[44:45], v[66:67], 0, s[36:37]
	v_mov_b64_e32 v[46:47], s[48:49]
	v_mad_u64_u32 v[32:33], s[14:15], v44, s45, v[46:47]
	v_mad_i32_i24 v33, v45, s45, v33
	v_lshl_add_u64 v[36:37], v[32:33], 0, v[70:71]
	v_add_u32_e32 v32, 0x100, v81
	v_ashrrev_i32_e32 v33, 31, v32
	v_lshrrev_b32_e32 v33, 29, v33
	v_add_u32_e32 v33, v32, v33
	v_ashrrev_i32_e32 v86, 3, v33
	v_and_b32_e32 v33, -8, v33
	v_sub_u32_e32 v85, v32, v33
	v_lshlrev_b32_e32 v32, 3, v85
	v_ashrrev_i32_e32 v33, 31, v32
	s_waitcnt vmcnt(2)
	v_add_u32_e32 v48, 0x200, v81
	v_lshlrev_b64 v[90:91], 1, v[32:33]
	v_ashrrev_i32_e32 v32, 31, v48
	v_lshrrev_b32_e32 v32, 29, v32
	v_add_u32_e32 v32, v48, v32
	v_ashrrev_i32_e32 v92, 3, v32
	v_and_b32_e32 v49, -8, v32
	v_add_u32_e32 v32, 0x300, v81
	v_ashrrev_i32_e32 v33, 31, v32
	v_lshrrev_b32_e32 v33, 29, v33
	v_ashrrev_i32_e32 v87, 31, v86
	v_add_u32_e32 v33, v32, v33
	v_lshl_add_u64 v[88:89], v[86:87], 0, s[36:37]
	v_ashrrev_i32_e32 v94, 3, v33
	v_and_b32_e32 v33, -8, v33
	v_mad_u64_u32 v[34:35], s[14:15], v88, s45, v[46:47]
	v_sub_u32_e32 v87, v32, v33
	v_ashrrev_i32_e32 v95, 31, v94
	v_mad_i32_i24 v35, v89, s45, v35
	v_lshlrev_b32_e32 v32, 3, v87
	v_lshl_add_u64 v[40:41], v[94:95], 0, s[36:37]
	v_lshl_add_u64 v[38:39], v[34:35], 0, v[90:91]
	v_mad_u64_u32 v[34:35], s[14:15], v40, s45, v[46:47]
	v_ashrrev_i32_e32 v33, 31, v32
	v_mad_i32_i24 v35, v41, s45, v35
	v_lshlrev_b64 v[42:43], 1, v[32:33]
	v_lshl_add_u64 v[32:33], v[34:35], 0, v[42:43]
	v_add_co_u32_e32 v32, vcc, s72, v32
	s_waitcnt lgkmcnt(0)
	s_nop 0
	v_addc_co_u32_e32 v33, vcc, 0, v33, vcc
	s_barrier
	global_load_dwordx4 v[32:35], v[32:33], off offset:512
	v_sub_u32_e32 v95, v48, v49
	v_ashrrev_i32_e32 v93, 31, v92
	v_lshlrev_b32_e32 v48, 3, v95
	v_lshl_add_u64 v[96:97], v[92:93], 0, s[36:37]
	v_mad_u64_u32 v[46:47], s[14:15], v96, s45, v[46:47]
	v_ashrrev_i32_e32 v49, 31, v48
	v_mad_i32_i24 v47, v97, s45, v47
	v_lshlrev_b64 v[98:99], 1, v[48:49]
	v_lshl_add_u64 v[100:101], v[46:47], 0, v[98:99]
	v_lshl_or_b32 v46, v75, 7, v128
	ds_read_b128 v[60:63], v46 offset:8704
	ds_read_b128 v[80:83], v46 offset:8768
	s_ashr_i32 s13, s16, 31
	s_add_u32 s12, s28, s16
	s_addc_u32 s13, s29, s13
	s_lshl_b32 s14, s83, 1
	s_add_u32 s12, s12, s14
	v_lshl_or_b32 v46, v84, 2, v64
	s_waitcnt lgkmcnt(0)
	v_mul_f32_e32 v69, v0, v80
	s_addc_u32 s13, s13, 0
	v_mul_lo_u32 v0, v66, s74
	v_mul_lo_u32 v46, v46, s74
	v_mul_f32_e32 v75, v1, v81
	v_lshl_add_u32 v66, v68, 2, v0
	v_mov_b64_e32 v[0:1], s[12:13]
	v_lshl_add_u32 v47, v73, 2, v46
	v_mul_f32_e32 v48, v16, v60
	v_mul_f32_e32 v49, v28, v60
	v_mul_f32_e32 v50, v24, v60
	v_mul_f32_e32 v51, v20, v60
	s_waitcnt vmcnt(1)
	v_mul_f32_e32 v52, v17, v61
	v_mul_f32_e32 v53, v29, v61
	v_mul_f32_e32 v54, v25, v61
	v_mul_f32_e32 v55, v21, v61
	v_mul_f32_e32 v56, v18, v62
	v_mul_f32_e32 v57, v30, v62
	v_mul_f32_e32 v58, v26, v62
	v_mul_f32_e32 v59, v22, v62
	v_mul_f32_e32 v60, v19, v63
	v_mul_f32_e32 v61, v31, v63
	v_mul_f32_e32 v62, v27, v63
	v_mul_f32_e32 v64, v23, v63
	v_mul_f32_e32 v63, v12, v80
	v_mul_f32_e32 v65, v8, v80
	v_mul_f32_e32 v67, v4, v80
	v_mul_f32_e32 v72, v13, v81
	v_mul_f32_e32 v73, v9, v81
	v_mul_f32_e32 v74, v5, v81
	v_mul_f32_e32 v76, v14, v82
	v_mul_f32_e32 v77, v10, v82
	v_mul_f32_e32 v78, v6, v82
	v_mul_f32_e32 v80, v2, v82
	v_mul_f32_e32 v79, v15, v83
	v_mul_f32_e32 v81, v11, v83
	v_mul_f32_e32 v82, v7, v83
	v_mul_f32_e32 v83, v3, v83
	v_mad_u64_u32 v[2:3], s[12:13], v44, s70, v[0:1]
	v_mad_i32_i24 v3, v45, s70, v3
	v_lshl_add_u64 v[12:13], v[2:3], 0, v[70:71]
	v_mul_lo_u32 v2, v86, s74
	v_lshl_add_u32 v46, v85, 5, v2
	v_mad_u64_u32 v[2:3], s[12:13], v88, s70, v[0:1]
	v_mad_i32_i24 v3, v89, s70, v3
	v_mad_u64_u32 v[4:5], s[12:13], v40, s70, v[0:1]
	v_lshl_add_u64 v[10:11], v[2:3], 0, v[90:91]
	v_mul_lo_u32 v2, v92, s74
	v_mad_i32_i24 v5, v41, s70, v5
	v_lshl_add_u32 v45, v95, 5, v2
	v_mad_u64_u32 v[2:3], s[12:13], v96, s70, v[0:1]
	v_lshl_add_u64 v[14:15], v[4:5], 0, v[42:43]
	v_mad_i32_i24 v3, v97, s70, v3
	v_add_co_u32_e32 v0, vcc, s72, v100
	v_lshl_add_u64 v[8:9], v[2:3], 0, v[98:99]
	v_mul_lo_u32 v2, v94, s74
	s_waitcnt vmcnt(0)
	v_lshlrev_b32_e32 v16, 16, v33
	v_lshlrev_b32_e32 v18, 16, v32
	v_mul_f32_e32 v6, 0xbfb8aa3b, v18
	v_mul_f32_e32 v7, 0xbfb8aa3b, v16
	v_exp_f32_e32 v6, v6
	v_exp_f32_e32 v7, v7
	v_addc_co_u32_e32 v1, vcc, 0, v101, vcc
	v_lshl_add_u32 v44, v87, 5, v2
	v_pk_add_f32 v[4:5], v[6:7], 1.0 op_sel_hi:[1,0]
	global_load_dwordx4 v[0:3], v[0:1], off offset:512
	v_and_b32_e32 v19, 0xffff0000, v33
	v_and_b32_e32 v20, 0xffff0000, v32
	v_mul_f32_e32 v6, 0xbfb8aa3b, v20
	v_rcp_f32_e32 v17, v5
	s_nop 0
	v_mul_f32_e32 v17, v16, v17
	v_mul_f32_e32 v7, 0xbfb8aa3b, v19
	v_exp_f32_e32 v6, v6
	v_exp_f32_e32 v7, v7
	s_nop 0
	v_pk_add_f32 v[6:7], v[6:7], 1.0 op_sel_hi:[1,0]
	v_rcp_f32_e32 v16, v4
	s_nop 0
	v_mul_f32_e32 v16, v18, v16
	v_lshlrev_b32_e32 v23, 16, v34
	v_rcp_f32_e32 v4, v7
	s_nop 0
	v_mul_f32_e32 v19, v19, v4
	v_lshlrev_b32_e32 v22, 16, v35
	v_mul_f32_e32 v4, 0xbfb8aa3b, v23
	v_mul_f32_e32 v5, 0xbfb8aa3b, v22
	v_exp_f32_e32 v4, v4
	v_exp_f32_e32 v5, v5
	v_rcp_f32_e32 v18, v6
	s_nop 0
	v_mul_f32_e32 v18, v20, v18
	v_and_b32_e32 v24, 0xffff0000, v35
	v_pk_add_f32 v[4:5], v[4:5], 1.0 op_sel_hi:[1,0]
	v_and_b32_e32 v25, 0xffff0000, v34
	v_mul_f32_e32 v6, 0xbfb8aa3b, v25
	v_exp_f32_e32 v6, v6
	v_rcp_f32_e32 v21, v5
	s_nop 0
	v_mul_f32_e32 v21, v22, v21
	v_mul_f32_e32 v7, 0xbfb8aa3b, v24
	v_exp_f32_e32 v7, v7
	s_nop 0
	v_pk_add_f32 v[6:7], v[6:7], 1.0 op_sel_hi:[1,0]
	v_rcp_f32_e32 v20, v4
	s_nop 0
	v_mul_f32_e32 v20, v23, v20
	v_rcp_f32_e32 v23, v7
	s_nop 0
	v_mul_f32_e32 v23, v24, v23
	s_waitcnt vmcnt(0)
; __device__ __forceinline__ unsigned pack2(float a, float b) { return (unsigned)f2bf(a) | ((unsigned)f2bf(b) << 16); }
; __device__ __forceinline__ float bflo(unsigned w) { return __uint_as_float(w << 16); }
; __device__ __forceinline__ float bfhi(unsigned w) { return __uint_as_float(w & 0xffff0000u); }
; __device__ __forceinline__ float silu_f(float g) { return g / (1.f + __expf(-g)); }
; template <int DH, int MODE>
; __device__ void attn_item(const Params& p, int layer, int b, int blk, int head, char* smem) {
;     ...
; #pragma unroll
;     for (int m = 0; m < 2; ++m)
; #pragma unroll
;       for (int j = 0; j < 4; ++j) {
;         int r = wid * 32 + m * 16 + fq * 4 + j;
; #pragma unroll
;         for (int n = 0; n < NDT; ++n) Of[r * OST + n * 16 + fr] = o[m][n][j] * lis[m][j];
;       }
;     __syncthreads();
; #pragma unroll
;     for (int i = 0; i < NCH; ++i) {
;       int q = tid + 256 * i, r = q / CPR, c = (q % CPR) * 8;
;       float4 m0 = *reinterpret_cast<const float4*>(Of + r * OST + c);
;       float4 m1 = *reinterpret_cast<const float4*>(Of + r * OST + c + 4);
;       float mm[8] = {m0.x, m0.y, m0.z, m0.w, m1.x, m1.y, m1.z, m1.w};
;       unsigned gw[4] = {gt[i].x, gt[i].y, gt[i].z, gt[i].w};
;       unsigned ow[4];
; #pragma unroll
;       for (int e = 0; e < 4; ++e)
;         ow[e] = pack2(mm[2 * e] * silu_f(bflo(gw[e])), mm[2 * e + 1] * silu_f(bfhi(gw[e])));
	v_lshlrev_b32_e32 v24, 16, v1
	v_lshlrev_b32_e32 v26, 16, v0
	v_mul_f32_e32 v4, 0xbfb8aa3b, v26
	v_mul_f32_e32 v5, 0xbfb8aa3b, v24
	v_exp_f32_e32 v4, v4
	v_exp_f32_e32 v5, v5
	v_and_b32_e32 v27, 0xffff0000, v1
	v_rcp_f32_e32 v22, v6
	s_nop 0
	v_mul_f32_e32 v22, v25, v22
	v_pk_add_f32 v[4:5], v[4:5], 1.0 op_sel_hi:[1,0]
	v_and_b32_e32 v28, 0xffff0000, v0
	v_mul_f32_e32 v0, 0xbfb8aa3b, v28
	v_exp_f32_e32 v6, v0
	v_lshlrev_b32_e32 v32, 16, v3
	v_mul_f32_e32 v7, 0xbfb8aa3b, v27
	v_rcp_f32_e32 v1, v5
	s_nop 0
	v_mul_f32_e32 v1, v24, v1
	v_exp_f32_e32 v7, v7
	s_nop 0
	v_pk_add_f32 v[24:25], v[6:7], 1.0 op_sel_hi:[1,0]
	v_rcp_f32_e32 v0, v4
	s_nop 0
	v_mul_f32_e32 v0, v26, v0
	v_lshlrev_b32_e32 v33, 16, v2
	v_rcp_f32_e32 v25, v25
	s_nop 0
	v_mul_f32_e32 v25, v27, v25
	v_add_co_u32_e64 v4, s[12:13], s72, v38
	s_nop 0
	s_nop 0
	v_addc_co_u32_e64 v5, s[12:13], 0, v39, s[12:13]
	global_load_dwordx4 v[4:7], v[4:5], off offset:512
	v_mul_f32_e32 v26, 0xbfb8aa3b, v33
	v_mul_f32_e32 v27, 0xbfb8aa3b, v32
	v_exp_f32_e32 v26, v26
	v_exp_f32_e32 v27, v27
	v_and_b32_e32 v30, 0xffff0000, v3
	v_rcp_f32_e32 v24, v24
	s_nop 0
	v_mul_f32_e32 v24, v28, v24
	v_pk_add_f32 v[26:27], v[26:27], 1.0 op_sel_hi:[1,0]
	v_and_b32_e32 v38, 0xffff0000, v2
	v_mul_f32_e32 v2, 0xbfb8aa3b, v38
	v_exp_f32_e32 v28, v2
	v_mul_f32_e32 v29, 0xbfb8aa3b, v30
	v_exp_f32_e32 v29, v29
	v_rcp_f32_e32 v3, v27
	s_nop 0
	v_mul_f32_e32 v3, v32, v3
	v_pk_add_f32 v[28:29], v[28:29], 1.0 op_sel_hi:[1,0]
	v_rcp_f32_e32 v2, v26
	s_nop 0
	v_mul_f32_e32 v2, v33, v2
	v_rcp_f32_e32 v27, v29
	s_nop 0
	v_mul_f32_e32 v27, v30, v27
	v_add_co_u32_e64 v30, s[12:13], s72, v36
	s_nop 0
	s_nop 0
	v_addc_co_u32_e64 v31, s[12:13], 0, v37, s[12:13]
	global_load_dwordx4 v[32:35], v[30:31], off offset:512
	v_rcp_f32_e32 v26, v28
	s_nop 0
	v_mul_f32_e32 v26, v38, v26
	s_barrier
	s_waitcnt vmcnt(1)
	v_lshlrev_b32_e32 v36, 16, v5
	v_lshlrev_b32_e32 v37, 16, v4
	v_mul_f32_e32 v30, 0xbfb8aa3b, v37
	v_mul_f32_e32 v31, 0xbfb8aa3b, v36
	v_exp_f32_e32 v30, v30
	v_exp_f32_e32 v31, v31
	v_and_b32_e32 v38, 0xffff0000, v5
	v_and_b32_e32 v39, 0xffff0000, v4
	v_mul_f32_e32 v4, 0xbfb8aa3b, v39
	v_pk_add_f32 v[28:29], v[30:31], 1.0 op_sel_hi:[1,0]
	v_exp_f32_e32 v30, v4
	ds_write2_b32 v47, v48, v49 offset1:16
	ds_write2_b32 v47, v50, v51 offset0:32 offset1:48
	ds_write2_b32 v47, v52, v53 offset0:68 offset1:84
	ds_write2_b32 v47, v54, v55 offset0:100 offset1:116
	ds_write2_b32 v47, v56, v57 offset0:136 offset1:152
	ds_write2_b32 v47, v58, v59 offset0:168 offset1:184
	ds_write2_b32 v47, v60, v61 offset0:204 offset1:220
	ds_write2_b32 v47, v62, v64 offset0:236 offset1:252
	v_mul_f32_e32 v31, 0xbfb8aa3b, v38
	v_exp_f32_e32 v31, v31
	v_rcp_f32_e32 v5, v29
	s_nop 0
	v_mul_f32_e32 v5, v36, v5
	v_pk_add_f32 v[30:31], v[30:31], 1.0 op_sel_hi:[1,0]
	v_rcp_f32_e32 v4, v28
	s_nop 0
	v_mul_f32_e32 v4, v37, v4
	v_rcp_f32_e32 v29, v31
	s_nop 0
	v_mul_f32_e32 v29, v38, v29
	v_lshlrev_b32_e32 v38, 16, v7
	v_lshlrev_b32_e32 v40, 16, v6
	v_mul_f32_e32 v36, 0xbfb8aa3b, v40
	v_mul_f32_e32 v37, 0xbfb8aa3b, v38
	v_exp_f32_e32 v36, v36
	v_exp_f32_e32 v37, v37
	v_rcp_f32_e32 v28, v30
	s_nop 0
	v_mul_f32_e32 v28, v39, v28
	v_and_b32_e32 v39, 0xffff0000, v7
	v_pk_add_f32 v[30:31], v[36:37], 1.0 op_sel_hi:[1,0]
	v_and_b32_e32 v41, 0xffff0000, v6
	v_mul_f32_e32 v6, 0xbfb8aa3b, v41
	v_exp_f32_e32 v36, v6
	v_mul_f32_e32 v37, 0xbfb8aa3b, v39
	v_exp_f32_e32 v37, v37
	v_rcp_f32_e32 v7, v31
	s_nop 0
	v_mul_f32_e32 v7, v38, v7
	v_pk_add_f32 v[36:37], v[36:37], 1.0 op_sel_hi:[1,0]
	v_rcp_f32_e32 v6, v30
	s_nop 0
	v_mul_f32_e32 v6, v40, v6
	v_rcp_f32_e32 v31, v37
	s_nop 0
	v_mul_f32_e32 v31, v39, v31
	s_waitcnt vmcnt(0)
	v_lshlrev_b32_e32 v42, 16, v33
	v_lshlrev_b32_e32 v43, 16, v32
	v_mul_f32_e32 v38, 0xbfb8aa3b, v43
	v_mul_f32_e32 v39, 0xbfb8aa3b, v42
	v_exp_f32_e32 v38, v38
	v_exp_f32_e32 v39, v39
	v_rcp_f32_e32 v30, v36
	s_nop 0
	v_mul_f32_e32 v30, v41, v30
	v_and_b32_e32 v68, 0xffff0000, v33
	v_pk_add_f32 v[36:37], v[38:39], 1.0 op_sel_hi:[1,0]
	v_and_b32_e32 v39, 0xffff0000, v32
	v_mul_f32_e32 v32, 0xbfb8aa3b, v39
	v_exp_f32_e32 v32, v32
	v_rcp_f32_e32 v41, v37
	s_nop 0
	v_mul_f32_e32 v41, v42, v41
	v_mul_f32_e32 v33, 0xbfb8aa3b, v68
	v_exp_f32_e32 v33, v33
	s_nop 0
	v_pk_add_f32 v[32:33], v[32:33], 1.0 op_sel_hi:[1,0]
	v_rcp_f32_e32 v40, v36
	s_nop 0
	v_mul_f32_e32 v40, v43, v40
	v_lshlrev_b32_e32 v70, 16, v34
	v_rcp_f32_e32 v43, v33
	s_nop 0
	v_mul_f32_e32 v43, v68, v43
	v_lshlrev_b32_e32 v38, 16, v35
	v_mul_f32_e32 v36, 0xbfb8aa3b, v70
	v_mul_f32_e32 v37, 0xbfb8aa3b, v38
	v_exp_f32_e32 v36, v36
	v_exp_f32_e32 v37, v37
	v_rcp_f32_e32 v42, v32
	s_nop 0
	v_mul_f32_e32 v42, v39, v42
	v_and_b32_e32 v39, 0xffff0000, v35
	v_pk_add_f32 v[32:33], v[36:37], 1.0 op_sel_hi:[1,0]
	v_and_b32_e32 v68, 0xffff0000, v34
	v_mul_f32_e32 v34, 0xbfb8aa3b, v68
	v_exp_f32_e32 v34, v34
	v_rcp_f32_e32 v71, v33
	s_nop 0
	v_mul_f32_e32 v71, v38, v71
	v_mul_f32_e32 v35, 0xbfb8aa3b, v39
	v_exp_f32_e32 v35, v35
	s_nop 0
	v_pk_add_f32 v[36:37], v[34:35], 1.0 op_sel_hi:[1,0]
	v_rcp_f32_e32 v33, v32
	s_nop 0
	v_mul_f32_e32 v70, v70, v33
	v_rcp_f32_e32 v85, v37
	s_nop 0
	v_mul_f32_e32 v85, v39, v85
	v_add_u32_e32 v32, 0x1000, v47
	ds_write2_b32 v32, v63, v65 offset0:64 offset1:80
	ds_write2_b32 v32, v67, v69 offset0:96 offset1:112
	ds_write2_b32 v32, v72, v73 offset0:132 offset1:148
	ds_write2_b32 v32, v74, v75 offset0:164 offset1:180
	ds_write2_b32 v32, v76, v77 offset0:200 offset1:216
	ds_write2_b32 v32, v78, v80 offset0:232 offset1:248
	v_add_u32_e32 v32, 0x1400, v47
	ds_write2_b32 v32, v79, v81 offset0:12 offset1:28
	ds_write2_b32 v32, v82, v83 offset0:44 offset1:60
	s_waitcnt lgkmcnt(0)
	s_barrier
; __device__ __forceinline__ unsigned pack2(float a, float b) { return (unsigned)f2bf(a) | ((unsigned)f2bf(b) << 16); }
; __device__ __forceinline__ float bflo(unsigned w) { return __uint_as_float(w << 16); }
; __device__ __forceinline__ float bfhi(unsigned w) { return __uint_as_float(w & 0xffff0000u); }
; __device__ __forceinline__ float silu_f(float g) { return g / (1.f + __expf(-g)); }
; template <int DH, int MODE>
; __device__ void attn_item(const Params& p, int layer, int b, int blk, int head, char* smem) {
;     ...
; #pragma unroll
;     for (int i = 0; i < NCH; ++i) {
;       int q = tid + 256 * i, r = q / CPR, c = (q % CPR) * 8;
;       float4 m0 = *reinterpret_cast<const float4*>(Of + r * OST + c);
;       float4 m1 = *reinterpret_cast<const float4*>(Of + r * OST + c + 4);
;       float mm[8] = {m0.x, m0.y, m0.z, m0.w, m1.x, m1.y, m1.z, m1.w};
;       unsigned gw[4] = {gt[i].x, gt[i].y, gt[i].z, gt[i].w};
;       unsigned ow[4];
; #pragma unroll
;       for (int e = 0; e < 4; ++e)
;         ow[e] = pack2(mm[2 * e] * silu_f(bflo(gw[e])), mm[2 * e + 1] * silu_f(bfhi(gw[e])));
;       *reinterpret_cast<uint4*>(Y + (tq0 + r) * YW + ycol + c) = make_uint4(ow[0], ow[1], ow[2], ow[3]);
;     }
	ds_read_b128 v[32:35], v66
	v_rcp_f32_e32 v84, v36
	s_nop 0
	v_mul_f32_e32 v84, v68, v84
	ds_read_b128 v[36:39], v66 offset:16
	v_add_co_u32_e32 v12, vcc, s77, v12
	s_waitcnt lgkmcnt(1)
	v_mov_b32_e32 v48, v32
	v_mov_b32_e32 v49, v34
	v_pk_mul_f32 v[40:41], v[40:41], v[48:49]
	v_mov_b32_e32 v34, v33
	v_pk_mul_f32 v[32:33], v[42:43], v[34:35]
	v_cvt_pk_bf16_f32 v35, 0, v40
	v_cvt_pk_bf16_f32 v34, 0, v41
	v_cvt_pk_bf16_f32 v33, 0, v33
	v_cvt_pk_bf16_f32 v32, 0, v32
	v_and_b32_e32 v33, 0xffff0000, v33
	v_and_b32_e32 v32, 0xffff0000, v32
	v_or_b32_sdwa v33, v33, v34 dst_sel:DWORD dst_unused:UNUSED_PAD src0_sel:DWORD src1_sel:WORD_1
	v_or_b32_sdwa v32, v32, v35 dst_sel:DWORD dst_unused:UNUSED_PAD src0_sel:DWORD src1_sel:WORD_1
	s_waitcnt lgkmcnt(0)
	v_mov_b32_e32 v34, v36
	v_mov_b32_e32 v35, v38
	v_pk_mul_f32 v[34:35], v[70:71], v[34:35]
	v_mov_b32_e32 v38, v37
	v_pk_mul_f32 v[36:37], v[84:85], v[38:39]
	v_cvt_pk_bf16_f32 v34, 0, v34
	v_cvt_pk_bf16_f32 v35, 0, v35
	v_cvt_pk_bf16_f32 v37, 0, v37
	v_cvt_pk_bf16_f32 v36, 0, v36
	v_and_b32_e32 v37, 0xffff0000, v37
	v_and_b32_e32 v36, 0xffff0000, v36
	v_or_b32_sdwa v35, v37, v35 dst_sel:DWORD dst_unused:UNUSED_PAD src0_sel:DWORD src1_sel:WORD_1
	v_or_b32_sdwa v34, v36, v34 dst_sel:DWORD dst_unused:UNUSED_PAD src0_sel:DWORD src1_sel:WORD_1
	ds_read_b128 v[36:39], v46
	v_addc_co_u32_e32 v13, vcc, 0, v13, vcc
	global_store_dwordx4 v[12:13], v[32:35], off offset:1024
	s_nop 0
	ds_read_b128 v[32:35], v46 offset:16
	s_waitcnt lgkmcnt(1)
	v_mov_b32_e32 v12, v36
	v_mov_b32_e32 v13, v38
	v_pk_mul_f32 v[4:5], v[4:5], v[12:13]
	v_mov_b32_e32 v38, v37
	v_pk_mul_f32 v[12:13], v[28:29], v[38:39]
	v_cvt_pk_bf16_f32 v4, 0, v4
	v_cvt_pk_bf16_f32 v5, 0, v5
	v_cvt_pk_bf16_f32 v13, 0, v13
	v_cvt_pk_bf16_f32 v12, 0, v12
	v_and_b32_e32 v13, 0xffff0000, v13
	v_and_b32_e32 v12, 0xffff0000, v12
	v_or_b32_sdwa v5, v13, v5 dst_sel:DWORD dst_unused:UNUSED_PAD src0_sel:DWORD src1_sel:WORD_1
	v_or_b32_sdwa v4, v12, v4 dst_sel:DWORD dst_unused:UNUSED_PAD src0_sel:DWORD src1_sel:WORD_1
	s_waitcnt lgkmcnt(0)
	v_mov_b32_e32 v12, v32
	v_mov_b32_e32 v13, v34
	v_pk_mul_f32 v[6:7], v[6:7], v[12:13]
	v_mov_b32_e32 v34, v33
	v_pk_mul_f32 v[12:13], v[30:31], v[34:35]
	v_cvt_pk_bf16_f32 v6, 0, v6
	v_cvt_pk_bf16_f32 v7, 0, v7
	v_cvt_pk_bf16_f32 v13, 0, v13
	v_cvt_pk_bf16_f32 v12, 0, v12
	ds_read_b128 v[28:31], v45
	v_and_b32_e32 v13, 0xffff0000, v13
	v_and_b32_e32 v12, 0xffff0000, v12
	v_add_co_u32_e32 v10, vcc, s77, v10
	v_or_b32_sdwa v7, v13, v7 dst_sel:DWORD dst_unused:UNUSED_PAD src0_sel:DWORD src1_sel:WORD_1
	v_or_b32_sdwa v6, v12, v6 dst_sel:DWORD dst_unused:UNUSED_PAD src0_sel:DWORD src1_sel:WORD_1
	v_addc_co_u32_e32 v11, vcc, 0, v11, vcc
	global_store_dwordx4 v[10:11], v[4:7], off offset:1024
	s_waitcnt lgkmcnt(0)
	v_mov_b32_e32 v10, v28
	v_mov_b32_e32 v11, v30
	ds_read_b128 v[4:7], v45 offset:16
	v_pk_mul_f32 v[0:1], v[0:1], v[10:11]
	v_mov_b32_e32 v30, v29
	v_pk_mul_f32 v[10:11], v[24:25], v[30:31]
	v_cvt_pk_bf16_f32 v0, 0, v0
	v_cvt_pk_bf16_f32 v1, 0, v1
	v_cvt_pk_bf16_f32 v11, 0, v11
	v_cvt_pk_bf16_f32 v10, 0, v10
	v_and_b32_e32 v11, 0xffff0000, v11
	v_and_b32_e32 v10, 0xffff0000, v10
	v_or_b32_sdwa v1, v11, v1 dst_sel:DWORD dst_unused:UNUSED_PAD src0_sel:DWORD src1_sel:WORD_1
	v_or_b32_sdwa v0, v10, v0 dst_sel:DWORD dst_unused:UNUSED_PAD src0_sel:DWORD src1_sel:WORD_1
	s_waitcnt lgkmcnt(0)
	v_mov_b32_e32 v10, v4
	v_mov_b32_e32 v11, v6
	v_pk_mul_f32 v[2:3], v[2:3], v[10:11]
	v_mov_b32_e32 v6, v5
	v_pk_mul_f32 v[4:5], v[26:27], v[6:7]
	v_cvt_pk_bf16_f32 v2, 0, v2
	v_cvt_pk_bf16_f32 v3, 0, v3
	v_cvt_pk_bf16_f32 v5, 0, v5
	v_cvt_pk_bf16_f32 v4, 0, v4
	v_and_b32_e32 v5, 0xffff0000, v5
	v_and_b32_e32 v4, 0xffff0000, v4
	v_or_b32_sdwa v3, v5, v3 dst_sel:DWORD dst_unused:UNUSED_PAD src0_sel:DWORD src1_sel:WORD_1
	v_or_b32_sdwa v2, v4, v2 dst_sel:DWORD dst_unused:UNUSED_PAD src0_sel:DWORD src1_sel:WORD_1
	ds_read_b128 v[4:7], v44
	v_add_co_u32_e32 v8, vcc, s77, v8
	s_nop 1
	v_addc_co_u32_e32 v9, vcc, 0, v9, vcc
	global_store_dwordx4 v[8:9], v[0:3], off offset:1024
	s_waitcnt lgkmcnt(0)
	v_mov_b32_e32 v8, v4
	v_mov_b32_e32 v9, v6
	ds_read_b128 v[0:3], v44 offset:16
	v_pk_mul_f32 v[8:9], v[16:17], v[8:9]
	v_mov_b32_e32 v6, v5
	v_pk_mul_f32 v[4:5], v[18:19], v[6:7]
	v_cvt_pk_bf16_f32 v7, 0, v8
	v_cvt_pk_bf16_f32 v6, 0, v9
	v_cvt_pk_bf16_f32 v5, 0, v5
	v_cvt_pk_bf16_f32 v4, 0, v4
	v_and_b32_e32 v5, 0xffff0000, v5
	v_and_b32_e32 v4, 0xffff0000, v4
	v_or_b32_sdwa v5, v5, v6 dst_sel:DWORD dst_unused:UNUSED_PAD src0_sel:DWORD src1_sel:WORD_1
	v_or_b32_sdwa v4, v4, v7 dst_sel:DWORD dst_unused:UNUSED_PAD src0_sel:DWORD src1_sel:WORD_1
	s_waitcnt lgkmcnt(0)
	v_mov_b32_e32 v6, v0
	v_mov_b32_e32 v7, v2
	v_pk_mul_f32 v[6:7], v[20:21], v[6:7]
	v_mov_b32_e32 v2, v1
	v_pk_mul_f32 v[0:1], v[22:23], v[2:3]
	v_cvt_pk_bf16_f32 v2, 0, v7
	v_cvt_pk_bf16_f32 v3, 0, v6
	v_cvt_pk_bf16_f32 v0, 0, v0
	v_cvt_pk_bf16_f32 v1, 0, v1
	v_and_b32_e32 v0, 0xffff0000, v0
	v_and_b32_e32 v1, 0xffff0000, v1
	v_or_b32_sdwa v6, v0, v3 dst_sel:DWORD dst_unused:UNUSED_PAD src0_sel:DWORD src1_sel:WORD_1
	v_add_co_u32_e32 v0, vcc, 0x184a1000, v14
	v_or_b32_sdwa v7, v1, v2 dst_sel:DWORD dst_unused:UNUSED_PAD src0_sel:DWORD src1_sel:WORD_1
	s_nop 0
	v_addc_co_u32_e32 v1, vcc, 0, v15, vcc
	global_store_dwordx4 v[0:1], v[4:7], off offset:1024
	s_barrier

; __device__ __forceinline__ unsigned pack2(float a, float b) { return (unsigned)f2bf(a) | ((unsigned)f2bf(b) << 16); }
; template <int DH, int MODE>
; __device__ void attn_item(const Params& p, int layer, int b, int blk, int head, char* smem) {
;     ...
; #pragma unroll 2
;         for (int c = 7; c >= 0; --c) {
;           float4 v = s4[c];
;           float e[4] = {v.x, v.y, v.z, v.w};
; #pragma unroll
;           for (int k = 3; k >= 0; --k) {
;             float z = e[k];
;             bool valid = (kpb + c * 4 + k) < qpos;
;             float sp = fmaxf(z, 0.f) + __builtin_amdgcn_logf(1.f + __builtin_amdgcn_exp2f(-fabsf(z)));
;             run += valid ? -sp : 0.f;
;             e[k] = z + run;
;           }
;           s4[c] = make_float4(e[0], e[1], e[2], e[3]);
;         }
;         float other = __shfl_xor(run, 1);
;         float offs = m_run + (half == 0 ? other : 0.f);
; #pragma unroll 2
;         for (int s8 = 0; s8 < 4; ++s8) {
;           float4 va = s4[2 * s8], vb = s4[2 * s8 + 1];
;           float e[8] = {va.x, va.y, va.z, va.w, vb.x, vb.y, vb.z, vb.w};
;           float pv[8];
; #pragma unroll
;           for (int k = 0; k < 8; ++k) {
;             bool valid = (kpb + s8 * 8 + k) < qpos;
;             pv[k] = valid ? __builtin_amdgcn_exp2f(e[k] + offs) : 0.f;
;           }
;           uint4 ov;
;           ov.x = pack2(pv[0], pv[1]); ov.y = pack2(pv[2], pv[3]);
;           ov.z = pack2(pv[4], pv[5]); ov.w = pack2(pv[6], pv[7]);
;           *reinterpret_cast<uint4*>(prow + s8 * 16) = ov;
;         }
.LBB0_847:
	ds_read_b128 v[150:153], v148 offset:16
	ds_read_b128 v[176:179], v148
	v_add_u32_e32 v149, s52, v173
	v_add_u32_e32 v182, 0x3fdd, v149
	v_cmp_lt_i32_e32 vcc, v182, v144
	s_waitcnt lgkmcnt(1)
	v_exp_f32_e64 v175, -|v151|
	v_exp_f32_e64 v184, -|v150|
	v_max_f32_e32 v183, 0, v151
	v_add_f32_e32 v175, 1.0, v175
	v_log_f32_e32 v175, v175
	v_add_f32_e32 v182, 1.0, v184
	v_exp_f32_e64 v184, -|v153|
	v_add_u32_e32 v147, 0x3fdc, v149
	v_add_f32_e32 v175, v183, v175
	v_log_f32_e32 v182, v182
	v_cndmask_b32_e64 v175, 0, -v175, vcc
	v_cmp_lt_i32_e32 vcc, v147, v144
	v_add_f32_e32 v147, 1.0, v184
	v_exp_f32_e64 v184, -|v152|
	v_log_f32_e32 v147, v147
	v_max_f32_e32 v183, 0, v150
	v_add_u32_e32 v180, 0x3fdf, v149
	v_add_f32_e32 v182, v183, v182
	v_cndmask_b32_e64 v182, 0, -v182, vcc
	v_max_f32_e32 v183, 0, v153
	v_cmp_lt_i32_e32 vcc, v180, v144
	v_add_f32_e32 v180, 1.0, v184
	v_add_f32_e32 v147, v183, v147
	v_log_f32_e32 v180, v180
	v_cndmask_b32_e64 v147, 0, -v147, vcc
	v_add_f32_e32 v147, v146, v147
	v_add_u32_e32 v181, 0x3fde, v149
	v_max_f32_e32 v146, 0, v152
	v_add_f32_e32 v146, v146, v180
	v_cmp_lt_i32_e32 vcc, v181, v144
	s_add_i32 s52, s52, -8
	s_cmpk_eq_i32 s52, 0xffe0
	v_cndmask_b32_e64 v146, 0, -v146, vcc
	v_add_f32_e32 v146, v146, v147
	v_pk_add_f32 v[152:153], v[152:153], v[146:147]
	v_add_f32_e32 v147, v175, v146
	v_add_f32_e32 v146, v182, v147
	v_pk_add_f32 v[150:151], v[150:151], v[146:147]
	ds_write_b128 v148, v[150:153] offset:16
	s_waitcnt lgkmcnt(1)
	v_exp_f32_e64 v150, -|v177|
	v_exp_f32_e64 v175, -|v176|
	v_add_u32_e32 v147, 0x3fd8, v149
	v_add_f32_e32 v150, 1.0, v150
	v_log_f32_e32 v150, v150
	v_add_u32_e32 v151, 0x3fdb, v149
	v_add_u32_e32 v152, 0x3fda, v149
	v_add_u32_e32 v149, 0x3fd9, v149
	v_max_f32_e32 v153, 0, v177
	v_add_f32_e32 v150, v153, v150
	v_cmp_lt_i32_e32 vcc, v149, v144
	v_max_f32_e32 v153, 0, v176
	s_nop 0
	v_cndmask_b32_e64 v149, 0, -v150, vcc
	v_add_f32_e32 v150, 1.0, v175
	v_exp_f32_e64 v175, -|v179|
	v_log_f32_e32 v150, v150
	v_cmp_lt_i32_e32 vcc, v147, v144
	v_add_f32_e32 v147, 1.0, v175
	v_exp_f32_e64 v175, -|v178|
	v_log_f32_e32 v147, v147
	v_add_f32_e32 v150, v153, v150
	v_cndmask_b32_e64 v150, 0, -v150, vcc
	v_max_f32_e32 v153, 0, v179
	v_cmp_lt_i32_e32 vcc, v151, v144
	v_add_f32_e32 v151, 1.0, v175
	v_add_f32_e32 v147, v153, v147
	v_log_f32_e32 v151, v151
	v_cndmask_b32_e64 v147, 0, -v147, vcc
	v_add_f32_e32 v147, v146, v147
	v_max_f32_e32 v146, 0, v178
	v_add_f32_e32 v146, v146, v151
	v_cmp_lt_i32_e32 vcc, v152, v144
	s_nop 1
	v_cndmask_b32_e64 v146, 0, -v146, vcc
	v_add_f32_e32 v146, v146, v147
	v_pk_add_f32 v[152:153], v[178:179], v[146:147]
	v_add_f32_e32 v147, v149, v146
	v_add_f32_e32 v146, v150, v147
	v_pk_add_f32 v[150:151], v[176:177], v[146:147]
	ds_write_b128 v148, v[150:153]
	v_subrev_u32_e32 v148, 32, v148
	s_cbranch_scc0 .LBB0_847
	ds_bpermute_b32 v147, v163, v146
	s_mov_b32 s88, 0
	v_mov_b32_e32 v175, v168
	v_mov_b32_e32 v177, v167
	s_waitcnt lgkmcnt(0)
	v_cndmask_b32_e64 v148, 0, v147, s[14:15]
	v_add_f32_e32 v176, v174, v148
	s_branch .LBB0_850
.LBB0_849:
	s_or_b64 exec, exec, s[52:53]
	s_waitcnt lgkmcnt(3)
	v_add_f32_e32 v152, v176, v152
	v_exp_f32_e32 v152, v152
	s_waitcnt lgkmcnt(1)
	v_add_f32_e32 v149, v176, v149
	v_exp_f32_e32 v149, v149
	v_add_u32_e32 v182, 0x3fc9, v178
	v_add_f32_e32 v151, v176, v151
	v_add_f32_e32 v148, v176, v148
	v_cmp_lt_i32_e32 vcc, v182, v144
	v_exp_f32_e32 v185, v151
	v_exp_f32_e32 v186, v148
	v_add_u32_e32 v148, 0x3fce, v178
	s_waitcnt lgkmcnt(0)
	v_add_f32_e32 v151, v176, v180
	v_cndmask_b32_e32 v152, 0, v152, vcc
	v_exp_f32_e32 v151, v151
	v_cmp_lt_i32_e32 vcc, v148, v144
	v_add_u32_e32 v148, 0x3fcf, v178
	v_add_f32_e32 v153, v176, v153
	v_cndmask_b32_e32 v149, 0, v149, vcc
	v_cmp_lt_i32_e32 vcc, v148, v144
	v_cvt_pk_bf16_f32 v148, 0, v179
	v_exp_f32_e32 v153, v153
	v_lshrrev_b32_e32 v148, 16, v148
	v_cvt_pk_bf16_f32 v152, 0, v152
	v_add_f32_e32 v150, v176, v150
	v_cndmask_b32_e32 v151, 0, v151, vcc
	v_and_or_b32 v148, v152, s54, v148
	v_or_b32_e32 v182, 2, v181
	v_exp_f32_e32 v150, v150
	v_cvt_pk_bf16_f32 v149, 0, v149
	v_or_b32_e32 v183, 4, v181
	v_lshrrev_b32_e32 v149, 16, v149
	v_cvt_pk_bf16_f32 v151, 0, v151
	v_cmp_lt_i32_e32 vcc, v182, v144
	v_or_b32_e32 v184, 5, v181
	v_or_b32_e32 v181, 3, v181
	v_and_or_b32 v151, v151, s54, v149
	v_cndmask_b32_e32 v149, 0, v153, vcc
	v_cmp_lt_i32_e32 vcc, v183, v131
	v_cvt_pk_bf16_f32 v149, 0, v149
	s_nop 0
	v_cndmask_b32_e32 v152, 0, v185, vcc
	v_cmp_lt_i32_e32 vcc, v181, v144
	v_cvt_pk_bf16_f32 v152, 0, v152
	s_nop 0
	v_cndmask_b32_e32 v150, 0, v150, vcc
	v_cmp_lt_i32_e32 vcc, v184, v131
	v_cvt_pk_bf16_f32 v150, 0, v150
	s_nop 0
	v_cndmask_b32_e32 v153, 0, v186, vcc
	v_cvt_pk_bf16_f32 v153, 0, v153
	v_and_b32_e32 v153, 0xffff0000, v153
	v_and_b32_e32 v178, 0xffff0000, v150
	v_or_b32_sdwa v150, v153, v152 dst_sel:DWORD dst_unused:UNUSED_PAD src0_sel:DWORD src1_sel:WORD_1
	v_or_b32_sdwa v149, v178, v149 dst_sel:DWORD dst_unused:UNUSED_PAD src0_sel:DWORD src1_sel:WORD_1
	s_add_i32 s88, s88, 16
	ds_write_b128 v175, v[148:151] offset:16
	v_add_u32_e32 v177, 64, v177
	s_cmp_eq_u32 s88, 32
	v_add_u32_e32 v175, 32, v175
	s_cbranch_scc1 .LBB0_855

; __device__ __forceinline__ unsigned pack2(float a, float b) { return (unsigned)f2bf(a) | ((unsigned)f2bf(b) << 16); }
; template <int DH, int MODE>
; __device__ void attn_item(const Params& p, int layer, int b, int blk, int head, char* smem) {
;     ...
; #pragma unroll 2
;         for (int s8 = 0; s8 < 4; ++s8) {
;           float4 va = s4[2 * s8], vb = s4[2 * s8 + 1];
;           float e[8] = {va.x, va.y, va.z, va.w, vb.x, vb.y, vb.z, vb.w};
;           float pv[8];
; #pragma unroll
;           for (int k = 0; k < 8; ++k) {
;             bool valid = (kpb + s8 * 8 + k) < qpos;
;             pv[k] = valid ? __builtin_amdgcn_exp2f(e[k] + offs) : 0.f;
;           }
;           uint4 ov;
;           ov.x = pack2(pv[0], pv[1]); ov.y = pack2(pv[2], pv[3]);
;           ov.z = pack2(pv[4], pv[5]); ov.w = pack2(pv[6], pv[7]);
;           *reinterpret_cast<uint4*>(prow + s8 * 16) = ov;
;         }
.LBB0_852:
	s_or_b64 exec, exec, s[52:53]
	s_waitcnt lgkmcnt(3)
	v_add_f32_e32 v152, v176, v152
	v_exp_f32_e32 v152, v152
	s_waitcnt lgkmcnt(1)
	v_add_f32_e32 v149, v176, v149
	v_exp_f32_e32 v149, v149
	v_add_u32_e32 v183, 0x3fc1, v178
	v_add_f32_e32 v151, v176, v151
	v_add_f32_e32 v148, v176, v148
	v_cmp_lt_i32_e32 vcc, v183, v144
	v_exp_f32_e32 v186, v151
	v_exp_f32_e32 v187, v148
	v_add_u32_e32 v148, 0x3fc6, v178
	s_waitcnt lgkmcnt(0)
	v_add_f32_e32 v151, v176, v180
	v_cndmask_b32_e32 v152, 0, v152, vcc
	v_exp_f32_e32 v151, v151
	v_cmp_lt_i32_e32 vcc, v148, v144
	v_add_u32_e32 v148, 0x3fc7, v178
	v_add_f32_e32 v153, v176, v153
	v_cndmask_b32_e32 v149, 0, v149, vcc
	v_cmp_lt_i32_e32 vcc, v148, v144
	v_cvt_pk_bf16_f32 v148, 0, v181
	v_exp_f32_e32 v153, v153
	v_lshrrev_b32_e32 v148, 16, v148
	v_cvt_pk_bf16_f32 v152, 0, v152
	v_add_f32_e32 v150, v176, v150
	v_cndmask_b32_e32 v151, 0, v151, vcc
	v_and_or_b32 v148, v152, s54, v148
	v_or_b32_e32 v183, 2, v182
	v_exp_f32_e32 v150, v150
	v_cvt_pk_bf16_f32 v149, 0, v149
	v_or_b32_e32 v184, 4, v182
	v_lshrrev_b32_e32 v149, 16, v149
	v_cvt_pk_bf16_f32 v151, 0, v151
	v_cmp_lt_i32_e32 vcc, v183, v144
	v_or_b32_e32 v185, 5, v182
	v_or_b32_e32 v182, 3, v182
	v_and_or_b32 v151, v151, s54, v149
	v_cndmask_b32_e32 v149, 0, v153, vcc
	v_cmp_lt_i32_e32 vcc, v184, v131
	v_cvt_pk_bf16_f32 v149, 0, v149
	s_nop 0
	v_cndmask_b32_e32 v152, 0, v186, vcc
	v_cmp_lt_i32_e32 vcc, v182, v144
	v_cvt_pk_bf16_f32 v152, 0, v152
	s_nop 0
	v_cndmask_b32_e32 v150, 0, v150, vcc
	v_cmp_lt_i32_e32 vcc, v185, v131
	v_cvt_pk_bf16_f32 v150, 0, v150
	s_nop 0
	v_cndmask_b32_e32 v153, 0, v187, vcc
	v_cvt_pk_bf16_f32 v153, 0, v153
	v_and_b32_e32 v153, 0xffff0000, v153
	v_and_b32_e32 v180, 0xffff0000, v150
	v_or_b32_sdwa v150, v153, v152 dst_sel:DWORD dst_unused:UNUSED_PAD src0_sel:DWORD src1_sel:WORD_1
	v_or_b32_sdwa v149, v180, v149 dst_sel:DWORD dst_unused:UNUSED_PAD src0_sel:DWORD src1_sel:WORD_1
	ds_write_b128 v175, v[148:151]
	ds_read2_b32 v[152:153], v177 offset0:9 offset1:10
	ds_read2_b32 v[150:151], v177 offset0:11 offset1:12
	ds_read2_b32 v[148:149], v177 offset0:13 offset1:14
	ds_read_b32 v180, v177 offset:60
	v_add_u32_e32 v181, 0x3fc8, v178
	v_cmp_lt_i32_e32 vcc, v181, v144
	s_and_saveexec_b64 s[52:53], vcc
	s_cbranch_execz .LBB0_849
	ds_read_b32 v179, v177 offset:32
	s_waitcnt lgkmcnt(0)
	v_add_f32_e32 v179, v176, v179
	v_exp_f32_e32 v179, v179
	s_branch .LBB0_849

; __device__ void convert_weights(const Params& p, int layer, char* smem) {
;     ...
;     } else {
;       int v = u - 2624;
;       for (int e = tid; e < 4096; e += 256) {
;         int idx = v * 4096 + e;
;         int t = (idx >> 7) & 127, s = idx & 127;
;         float w = p.gm_w_s[(size_t)layer * 65536 + idx];
;         Ws_bf[idx] = (s <= t) ? f2bf(w) : (u16)0;
;       }
.LBB0_1012:
	v_add_u32_e32 v13, s44, v9
	v_bfe_u32 v13, v13, 7, 7
	v_cmp_le_u32_e32 vcc, v21, v13
	v_mov_b32_e32 v13, 0
	s_and_saveexec_b64 s[38:39], vcc
	s_cbranch_execz .LBB0_1011
	global_load_dword v13, v[14:15], off
	s_waitcnt vmcnt(0)
	v_cvt_pk_bf16_f32 v13, 0, v13
	v_lshrrev_b32_e32 v13, 16, v13
	s_branch .LBB0_1011

; __device__ __forceinline__ unsigned pack2(float a, float b) { return (unsigned)f2bf(a) | ((unsigned)f2bf(b) << 16); }
; __device__ void convert_weights(const Params& p, int layer, char* smem) {
;     ...
;     __syncthreads();
; #pragma unroll
;     for (int i = 0; i < 4; ++i) {
;       int kk = (tid >> 4) + 16 * i, nn = (tid & 15) * 4;
;       float4 v = *reinterpret_cast<const float4*>(src + (size_t)(kt * 64 + kk) * N + nt * 64 + nn);
;       tile[kk * 65 + nn + 0] = v.x; tile[kk * 65 + nn + 1] = v.y;
;       tile[kk * 65 + nn + 2] = v.z; tile[kk * 65 + nn + 3] = v.w;
;     }
;     __syncthreads();
; #pragma unroll
;     for (int i = 0; i < 2; ++i) {
;       int nn = (tid >> 3) + 32 * i, kk0 = (tid & 7) * 8;
;       uint4 o;
;       o.x = pack2(tile[(kk0 + 0) * 65 + nn], tile[(kk0 + 1) * 65 + nn]);
;       o.y = pack2(tile[(kk0 + 2) * 65 + nn], tile[(kk0 + 3) * 65 + nn]);
;       o.z = pack2(tile[(kk0 + 4) * 65 + nn], tile[(kk0 + 5) * 65 + nn]);
;       o.w = pack2(tile[(kk0 + 6) * 65 + nn], tile[(kk0 + 7) * 65 + nn]);
;       *reinterpret_cast<uint4*>(dst + (size_t)(nt * 64 + nn) * K + kt * 64 + kk0) = o;
;     }
.LBB0_1023:
	s_andn2_b64 vcc, exec, s[36:37]
	s_cbranch_vccnz .LBB0_1005
	s_lshl_b32 s42, s51, 6
	s_ashr_i32 s43, s42, 31
	s_lshl_b32 s36, s50, 6
	s_lshl_b64 s[50:51], s[42:43], 2
	s_add_u32 s38, s38, s50
	v_add_u32_e32 v9, s36, v19
	s_addc_u32 s39, s39, s51
	v_add_u32_e32 v13, 16, v9
	v_lshl_add_u64 v[16:17], s[38:39], 0, v[0:1]
	v_mad_i64_i32 v[32:33], s[38:39], s40, v9, 0
	v_mad_i64_i32 v[34:35], s[38:39], s40, v13, 0
	v_lshl_add_u64 v[32:33], v[32:33], 2, v[16:17]
	v_lshl_add_u64 v[36:37], v[34:35], 2, v[16:17]
	s_barrier
	global_load_dwordx4 v[32:35], v[32:33], off
	s_nop 0
	global_load_dwordx4 v[36:39], v[36:37], off
	v_add_u32_e32 v13, 32, v9
	v_mad_i64_i32 v[40:41], s[38:39], s40, v13, 0
	v_lshl_add_u64 v[40:41], v[40:41], 2, v[16:17]
	v_add_u32_e32 v9, 48, v9
	global_load_dwordx4 v[40:43], v[40:41], off
	v_mad_i64_i32 v[44:45], s[38:39], s40, v9, 0
	v_lshl_add_u64 v[16:17], v[44:45], 2, v[16:17]
	global_load_dwordx4 v[44:47], v[16:17], off
	v_add_u32_e32 v9, s42, v20
	v_ashrrev_i32_e32 v48, 31, v9
	v_mul_lo_u32 v50, s27, v9
	v_mad_u64_u32 v[16:17], s[38:39], s26, v9, 0
	v_add_u32_e32 v9, 32, v9
	v_ashrrev_i32_e32 v52, 31, v9
	s_ashr_i32 s37, s36, 31
	v_mov_b32_e32 v13, v1
	v_mul_lo_u32 v51, s26, v48
	v_mul_lo_u32 v53, s27, v9
	v_mad_u64_u32 v[48:49], s[38:39], s26, v9, 0
	v_mul_lo_u32 v9, s26, v52
	v_lshl_add_u64 v[14:15], s[36:37], 1, v[14:15]
	v_add3_u32 v17, v17, v51, v50
	v_add3_u32 v49, v49, v9, v53
	v_lshl_add_u64 v[14:15], v[14:15], 0, v[12:13]
	v_lshl_add_u64 v[50:51], v[16:17], 1, v[14:15]
	v_lshl_add_u64 v[48:49], v[48:49], 1, v[14:15]
	s_waitcnt vmcnt(3)
	ds_write2_b32 v23, v32, v33 offset1:1
	ds_write2_b32 v23, v34, v35 offset0:2 offset1:3
	s_waitcnt vmcnt(2)
	ds_write2_b32 v24, v36, v37 offset1:1
	ds_write2_b32 v25, v38, v39 offset1:1
	s_waitcnt vmcnt(1)
	ds_write2_b32 v26, v40, v41 offset1:1
	ds_write2_b32 v27, v42, v43 offset1:1
	s_waitcnt vmcnt(0)
	ds_write2_b32 v28, v44, v45 offset1:1
	ds_write2_b32 v29, v46, v47 offset1:1
	s_waitcnt lgkmcnt(0)
	s_barrier
	ds_read2_b32 v[14:15], v22 offset1:32
	ds_read2_b32 v[32:33], v22 offset0:65 offset1:97
	ds_read2_b32 v[34:35], v22 offset0:130 offset1:162
	ds_read2_b32 v[36:37], v22 offset0:195 offset1:227
	ds_read2_b32 v[38:39], v30 offset0:4 offset1:36
	ds_read2_b32 v[40:41], v30 offset0:69 offset1:101
	ds_read2_b32 v[42:43], v30 offset0:134 offset1:166
	ds_read2_b32 v[44:45], v30 offset0:199 offset1:231
	s_waitcnt lgkmcnt(7)
	s_waitcnt lgkmcnt(4)
	s_waitcnt lgkmcnt(0)
	v_cvt_pk_bf16_f32 v13, 0, v14
	v_cvt_pk_bf16_f32 v14, 0, v36
	v_cvt_pk_bf16_f32 v16, 0, v32
	v_cvt_pk_bf16_f32 v9, 0, v34
	v_cvt_pk_bf16_f32 v34, 0, v44
	v_cvt_pk_bf16_f32 v36, 0, v40
	v_and_b32_e32 v14, 0xffff0000, v14
	v_and_b32_e32 v16, 0xffff0000, v16
	v_cvt_pk_bf16_f32 v32, 0, v38
	v_cvt_pk_bf16_f32 v17, 0, v42
	v_cvt_pk_bf16_f32 v38, 0, v15
	v_and_b32_e32 v34, 0xffff0000, v34
	v_and_b32_e32 v36, 0xffff0000, v36
	v_or_b32_sdwa v15, v14, v9 dst_sel:DWORD dst_unused:UNUSED_PAD src0_sel:DWORD src1_sel:WORD_1
	v_or_b32_sdwa v14, v16, v13 dst_sel:DWORD dst_unused:UNUSED_PAD src0_sel:DWORD src1_sel:WORD_1
	v_or_b32_sdwa v17, v34, v17 dst_sel:DWORD dst_unused:UNUSED_PAD src0_sel:DWORD src1_sel:WORD_1
	v_or_b32_sdwa v16, v36, v32 dst_sel:DWORD dst_unused:UNUSED_PAD src0_sel:DWORD src1_sel:WORD_1
	v_cvt_pk_bf16_f32 v13, 0, v37
	global_store_dwordx4 v[50:51], v[14:17], off
	v_cvt_pk_bf16_f32 v9, 0, v35
	v_and_b32_e32 v13, 0xffff0000, v13
	v_cvt_pk_bf16_f32 v14, 0, v33
	v_or_b32_sdwa v15, v13, v9 dst_sel:DWORD dst_unused:UNUSED_PAD src0_sel:DWORD src1_sel:WORD_1
	v_cvt_pk_bf16_f32 v16, 0, v45
	v_cvt_pk_bf16_f32 v17, 0, v41
	v_and_b32_e32 v14, 0xffff0000, v14
	v_cvt_pk_bf16_f32 v13, 0, v39
	v_cvt_pk_bf16_f32 v9, 0, v43
	v_and_b32_e32 v16, 0xffff0000, v16
	v_and_b32_e32 v32, 0xffff0000, v17
	v_or_b32_sdwa v14, v14, v38 dst_sel:DWORD dst_unused:UNUSED_PAD src0_sel:DWORD src1_sel:WORD_1
	v_or_b32_sdwa v17, v16, v9 dst_sel:DWORD dst_unused:UNUSED_PAD src0_sel:DWORD src1_sel:WORD_1
	v_or_b32_sdwa v16, v32, v13 dst_sel:DWORD dst_unused:UNUSED_PAD src0_sel:DWORD src1_sel:WORD_1
	global_store_dwordx4 v[48:49], v[14:17], off
	s_branch .LBB0_1005

; template <int WM, int WN>
; __device__ __forceinline__ void store_tile_bf16(const f32x4 (&acc)[WM][WN], u16* dst, int ld, char* smem) {
;   constexpr int BM = 32 * WM, BN = 32 * WN, STR = BN + 8;
;   const int tid = opaque_tid(), lane = tid & 63, wid = tid >> 6;
;   const int wr = wid >> 1, wc = wid & 1, fr = lane & 15, fq = lane >> 4;
;   u16* T = reinterpret_cast<u16*>(smem);
; #pragma unroll
;   for (int m = 0; m < WM; ++m)
; #pragma unroll
;     for (int n = 0; n < WN; ++n)
; #pragma unroll
;       for (int j = 0; j < 4; ++j)
;         T[(wr * 16 * WM + m * 16 + fq * 4 + j) * STR + wc * 16 * WN + n * 16 + fr] = f2bf(acc[m][n][j]);
;   __syncthreads();
;   constexpr int CPR = BN / 8;
; #pragma unroll
;   for (int i = 0; i < BM * CPR / 256; ++i) {
;     int q = tid + 256 * i, row = q / CPR, c = q % CPR;
;     uint4 v = *reinterpret_cast<const uint4*>(T + row * STR + c * 8);
;     *reinterpret_cast<uint4*>(dst + (size_t)row * ld + c * 8) = v;
.LBB0_1065:
	v_mov_b32_e32 v64, v232
	v_lshrrev_b32_e32 v66, 2, v64
	s_waitcnt lgkmcnt(0)
	v_lshrrev_b32_e32 v65, 1, v64
	v_and_b32_e32 v66, 12, v66
	v_and_or_b32 v65, v65, s46, v66
	v_and_b32_e32 v66, 0x4f, v64
	v_mul_lo_u32 v65, v65, s49
	v_cvt_pk_bf16_f32 v44, 0, v44
	v_lshl_add_u32 v65, v66, 1, v65
	ds_write_b16_d16_hi v65, v44
	v_cvt_pk_bf16_f32 v44, 0, v45
	ds_write_b16_d16_hi v65, v44 offset:272
	v_cvt_pk_bf16_f32 v44, 0, v46
	ds_write_b16_d16_hi v65, v44 offset:544
	v_cvt_pk_bf16_f32 v44, 0, v47
	ds_write_b16_d16_hi v65, v44 offset:816
	v_cvt_pk_bf16_f32 v40, 0, v40
	ds_write_b16_d16_hi v65, v40 offset:32
	v_cvt_pk_bf16_f32 v40, 0, v41
	ds_write_b16_d16_hi v65, v40 offset:304
	v_cvt_pk_bf16_f32 v40, 0, v42
	ds_write_b16_d16_hi v65, v40 offset:576
	v_cvt_pk_bf16_f32 v40, 0, v43
	ds_write_b16_d16_hi v65, v40 offset:848
	v_cvt_pk_bf16_f32 v36, 0, v36
	ds_write_b16_d16_hi v65, v36 offset:64
	v_cvt_pk_bf16_f32 v36, 0, v37
	ds_write_b16_d16_hi v65, v36 offset:336
	v_cvt_pk_bf16_f32 v36, 0, v38
	ds_write_b16_d16_hi v65, v36 offset:608
	v_cvt_pk_bf16_f32 v36, 0, v39
	ds_write_b16_d16_hi v65, v36 offset:880
	v_cvt_pk_bf16_f32 v32, 0, v32
	ds_write_b16_d16_hi v65, v32 offset:96
	v_cvt_pk_bf16_f32 v32, 0, v33
	ds_write_b16_d16_hi v65, v32 offset:368
	v_cvt_pk_bf16_f32 v32, 0, v34
	ds_write_b16_d16_hi v65, v32 offset:640
	v_cvt_pk_bf16_f32 v32, 0, v35
	ds_write_b16_d16_hi v65, v32 offset:912
	v_cvt_pk_bf16_f32 v28, 0, v28
	ds_write_b16_d16_hi v65, v28 offset:4352
	v_cvt_pk_bf16_f32 v28, 0, v29
	ds_write_b16_d16_hi v65, v28 offset:4624
	v_cvt_pk_bf16_f32 v28, 0, v30
	ds_write_b16_d16_hi v65, v28 offset:4896
	v_cvt_pk_bf16_f32 v28, 0, v31
	ds_write_b16_d16_hi v65, v28 offset:5168
	v_cvt_pk_bf16_f32 v24, 0, v24
	ds_write_b16_d16_hi v65, v24 offset:4384
	v_cvt_pk_bf16_f32 v24, 0, v25
	ds_write_b16_d16_hi v65, v24 offset:4656
	v_cvt_pk_bf16_f32 v24, 0, v26
	ds_write_b16_d16_hi v65, v24 offset:4928
	v_cvt_pk_bf16_f32 v24, 0, v27
	ds_write_b16_d16_hi v65, v24 offset:5200
	v_cvt_pk_bf16_f32 v20, 0, v20
	ds_write_b16_d16_hi v65, v20 offset:4416
	v_cvt_pk_bf16_f32 v20, 0, v21
	ds_write_b16_d16_hi v65, v20 offset:4688
	v_cvt_pk_bf16_f32 v20, 0, v22
	ds_write_b16_d16_hi v65, v20 offset:4960
	v_cvt_pk_bf16_f32 v20, 0, v23
	ds_write_b16_d16_hi v65, v20 offset:5232
	v_cvt_pk_bf16_f32 v16, 0, v16
	ds_write_b16_d16_hi v65, v16 offset:4448
	v_cvt_pk_bf16_f32 v16, 0, v17
	ds_write_b16_d16_hi v65, v16 offset:4720
	v_cvt_pk_bf16_f32 v16, 0, v18
	ds_write_b16_d16_hi v65, v16 offset:4992
	v_cvt_pk_bf16_f32 v16, 0, v19
	ds_write_b16_d16_hi v65, v16 offset:5264
	v_cvt_pk_bf16_f32 v12, 0, v12
	ds_write_b16_d16_hi v65, v12 offset:8704
	v_cvt_pk_bf16_f32 v12, 0, v13
	ds_write_b16_d16_hi v65, v12 offset:8976
	v_cvt_pk_bf16_f32 v12, 0, v14
	ds_write_b16_d16_hi v65, v12 offset:9248
	v_cvt_pk_bf16_f32 v12, 0, v15
	ds_write_b16_d16_hi v65, v12 offset:9520
	v_cvt_pk_bf16_f32 v8, 0, v8
	ds_write_b16_d16_hi v65, v8 offset:8736
	v_cvt_pk_bf16_f32 v8, 0, v9
	ds_write_b16_d16_hi v65, v8 offset:9008
	v_cvt_pk_bf16_f32 v8, 0, v10
	ds_write_b16_d16_hi v65, v8 offset:9280
	v_cvt_pk_bf16_f32 v8, 0, v11
	ds_write_b16_d16_hi v65, v8 offset:9552
	v_cvt_pk_bf16_f32 v4, 0, v4
	ds_write_b16_d16_hi v65, v4 offset:8768
	v_cvt_pk_bf16_f32 v4, 0, v5
	ds_write_b16_d16_hi v65, v4 offset:9040
	v_cvt_pk_bf16_f32 v4, 0, v6
	ds_write_b16_d16_hi v65, v4 offset:9312
	v_cvt_pk_bf16_f32 v4, 0, v7
	ds_write_b16_d16_hi v65, v4 offset:9584
	v_cvt_pk_bf16_f32 v0, 0, v0
	ds_write_b16_d16_hi v65, v0 offset:8800
	v_cvt_pk_bf16_f32 v0, 0, v1
	ds_write_b16_d16_hi v65, v0 offset:9072
	v_cvt_pk_bf16_f32 v0, 0, v2
	ds_write_b16_d16_hi v65, v0 offset:9344
	v_cvt_pk_bf16_f32 v0, 0, v3
	ds_write_b16_d16_hi v65, v0 offset:9616
	v_cvt_pk_bf16_f32 v0, 0, v60
	ds_write_b16_d16_hi v65, v0 offset:13056
	v_cvt_pk_bf16_f32 v0, 0, v61
	ds_write_b16_d16_hi v65, v0 offset:13328
	v_cvt_pk_bf16_f32 v0, 0, v62
	ds_write_b16_d16_hi v65, v0 offset:13600
	v_cvt_pk_bf16_f32 v0, 0, v63
	ds_write_b16_d16_hi v65, v0 offset:13872
	v_cvt_pk_bf16_f32 v0, 0, v56
	ds_write_b16_d16_hi v65, v0 offset:13088
	v_cvt_pk_bf16_f32 v0, 0, v57
	ds_write_b16_d16_hi v65, v0 offset:13360
	v_cvt_pk_bf16_f32 v0, 0, v58
	ds_write_b16_d16_hi v65, v0 offset:13632
	v_cvt_pk_bf16_f32 v0, 0, v59
	ds_write_b16_d16_hi v65, v0 offset:13904
	v_cvt_pk_bf16_f32 v0, 0, v52
	ds_write_b16_d16_hi v65, v0 offset:13120
	v_cvt_pk_bf16_f32 v0, 0, v53
	ds_write_b16_d16_hi v65, v0 offset:13392
	v_cvt_pk_bf16_f32 v0, 0, v54
	ds_write_b16_d16_hi v65, v0 offset:13664
	v_cvt_pk_bf16_f32 v0, 0, v55
	ds_write_b16_d16_hi v65, v0 offset:13936
	v_cvt_pk_bf16_f32 v0, 0, v48
	ds_write_b16_d16_hi v65, v0 offset:13152
	v_cvt_pk_bf16_f32 v0, 0, v49
	ds_write_b16_d16_hi v65, v0 offset:13424
	v_cvt_pk_bf16_f32 v0, 0, v50
	ds_write_b16_d16_hi v65, v0 offset:13696
	s_lshl_b32 s16, s16, 7
	s_mul_hi_i32 s12, s14, 0x130000
	s_mul_i32 s14, s14, 0x130000
	v_cvt_pk_bf16_f32 v0, 0, v51
	s_add_u32 s20, s36, s14
	ds_write_b16_d16_hi v65, v0 offset:13968
	v_ashrrev_i32_e32 v0, 31, v64
	s_addc_u32 s12, s37, s12
	s_ashr_i32 s17, s16, 31
	v_lshrrev_b32_e32 v0, 28, v0
	s_lshl_b64 s[14:15], s[16:17], 1
	v_add_u32_e32 v0, v64, v0
	s_add_u32 s14, s20, s14
	v_ashrrev_i32_e32 v6, 4, v0
	v_and_b32_e32 v0, -16, v0
	s_addc_u32 s15, s12, s15
	v_sub_u32_e32 v0, v64, v0
	v_lshlrev_b32_e32 v4, 3, v0
	v_mov_b64_e32 v[8:9], s[14:15]
	v_mul_lo_u32 v1, v6, s49
	v_ashrrev_i32_e32 v5, 31, v4
	v_mad_i64_i32 v[6:7], s[14:15], v6, s50, v[8:9]
	v_lshl_add_u64 v[10:11], v[4:5], 1, v[6:7]
	v_add_u32_e32 v4, 0x100, v64
	v_ashrrev_i32_e32 v5, 31, v4
	v_lshrrev_b32_e32 v5, 28, v5
	v_lshl_add_u32 v0, v0, 4, v1
	v_add_u32_e32 v5, v4, v5
	s_waitcnt lgkmcnt(0)
	s_barrier
; template <int WM, int WN>
; __device__ __forceinline__ void store_tile_bf16(const f32x4 (&acc)[WM][WN], u16* dst, int ld, char* smem) {
;     ...
;   constexpr int CPR = BN / 8;
; #pragma unroll
;   for (int i = 0; i < BM * CPR / 256; ++i) {
;     int q = tid + 256 * i, row = q / CPR, c = q % CPR;
;     uint4 v = *reinterpret_cast<const uint4*>(T + row * STR + c * 8);
;     *reinterpret_cast<uint4*>(dst + (size_t)row * ld + c * 8) = v;
;   }
	ds_read_b128 v[0:3], v0
	v_ashrrev_i32_e32 v12, 4, v5
	v_and_b32_e32 v5, -16, v5
	v_sub_u32_e32 v13, v4, v5
	v_mul_lo_u32 v4, v12, s49
	v_lshl_add_u32 v4, v13, 4, v4
	ds_read_b128 v[4:7], v4
	s_waitcnt lgkmcnt(1)
	global_store_dwordx4 v[10:11], v[0:3], off
	s_add_i32 s51, s51, s61
	s_cmp_lt_i32 s51, s47
	v_lshlrev_b32_e32 v0, 3, v13
	v_ashrrev_i32_e32 v1, 31, v0
	v_mad_i64_i32 v[2:3], s[14:15], v12, s50, v[8:9]
	v_lshl_add_u64 v[0:1], v[0:1], 1, v[2:3]
	s_waitcnt lgkmcnt(0)
	global_store_dwordx4 v[0:1], v[4:7], off
	v_add_u32_e32 v0, 0x200, v64
	v_ashrrev_i32_e32 v1, 31, v0
	v_lshrrev_b32_e32 v1, 28, v1
	v_add_u32_e32 v1, v0, v1
	v_ashrrev_i32_e32 v6, 4, v1
	v_and_b32_e32 v1, -16, v1
	v_sub_u32_e32 v0, v0, v1
	v_lshlrev_b32_e32 v4, 3, v0
	v_mul_lo_u32 v1, v6, s49
	v_ashrrev_i32_e32 v5, 31, v4
	v_mad_i64_i32 v[6:7], s[14:15], v6, s50, v[8:9]
	v_lshl_add_u64 v[10:11], v[4:5], 1, v[6:7]
	v_add_u32_e32 v4, 0x300, v64
	v_ashrrev_i32_e32 v5, 31, v4
	v_lshrrev_b32_e32 v5, 28, v5
	v_lshl_add_u32 v0, v0, 4, v1
	v_add_u32_e32 v5, v4, v5
	ds_read_b128 v[0:3], v0
	v_ashrrev_i32_e32 v12, 4, v5
	v_and_b32_e32 v5, -16, v5
	v_sub_u32_e32 v13, v4, v5
	v_mul_lo_u32 v4, v12, s49
	v_lshl_add_u32 v4, v13, 4, v4
	ds_read_b128 v[4:7], v4
	s_waitcnt lgkmcnt(1)
	global_store_dwordx4 v[10:11], v[0:3], off
	s_nop 1
	v_lshlrev_b32_e32 v0, 3, v13
	v_ashrrev_i32_e32 v1, 31, v0
	v_mad_i64_i32 v[2:3], s[14:15], v12, s50, v[8:9]
	v_lshl_add_u64 v[0:1], v[0:1], 1, v[2:3]
	s_waitcnt lgkmcnt(0)
	global_store_dwordx4 v[0:1], v[4:7], off
	v_add_u32_e32 v0, 0x400, v64
	v_ashrrev_i32_e32 v1, 31, v0
	v_lshrrev_b32_e32 v1, 28, v1
	v_add_u32_e32 v1, v0, v1
	v_ashrrev_i32_e32 v6, 4, v1
	v_and_b32_e32 v1, -16, v1
	v_sub_u32_e32 v0, v0, v1
	v_lshlrev_b32_e32 v4, 3, v0
	v_mul_lo_u32 v1, v6, s49
	v_ashrrev_i32_e32 v5, 31, v4
	v_mad_i64_i32 v[6:7], s[14:15], v6, s50, v[8:9]
	v_lshl_add_u64 v[10:11], v[4:5], 1, v[6:7]
	v_add_u32_e32 v4, 0x500, v64
	v_ashrrev_i32_e32 v5, 31, v4
	v_lshrrev_b32_e32 v5, 28, v5
	v_lshl_add_u32 v0, v0, 4, v1
	v_add_u32_e32 v5, v4, v5
	ds_read_b128 v[0:3], v0
	v_ashrrev_i32_e32 v12, 4, v5
	v_and_b32_e32 v5, -16, v5
	v_sub_u32_e32 v13, v4, v5
	v_mul_lo_u32 v4, v12, s49
	v_lshl_add_u32 v4, v13, 4, v4
	ds_read_b128 v[4:7], v4
	s_waitcnt lgkmcnt(1)
	global_store_dwordx4 v[10:11], v[0:3], off
	s_nop 1
	v_lshlrev_b32_e32 v0, 3, v13
	v_ashrrev_i32_e32 v1, 31, v0
	v_mad_i64_i32 v[2:3], s[14:15], v12, s50, v[8:9]
	v_lshl_add_u64 v[0:1], v[0:1], 1, v[2:3]
	s_waitcnt lgkmcnt(0)
	global_store_dwordx4 v[0:1], v[4:7], off
	v_add_u32_e32 v0, 0x600, v64
	v_ashrrev_i32_e32 v1, 31, v0
	v_lshrrev_b32_e32 v1, 28, v1
	v_add_u32_e32 v1, v0, v1
	v_ashrrev_i32_e32 v6, 4, v1
	v_and_b32_e32 v1, -16, v1
	v_sub_u32_e32 v0, v0, v1
	v_lshlrev_b32_e32 v4, 3, v0
	v_mul_lo_u32 v1, v6, s49
	v_ashrrev_i32_e32 v5, 31, v4
	v_mad_i64_i32 v[6:7], s[14:15], v6, s50, v[8:9]
	v_lshl_add_u64 v[10:11], v[4:5], 1, v[6:7]
	v_add_u32_e32 v4, 0x700, v64
	v_ashrrev_i32_e32 v5, 31, v4
	v_lshrrev_b32_e32 v5, 28, v5
	v_lshl_add_u32 v0, v0, 4, v1
	v_add_u32_e32 v5, v4, v5
	ds_read_b128 v[0:3], v0
	v_ashrrev_i32_e32 v12, 4, v5
	v_and_b32_e32 v5, -16, v5
	v_sub_u32_e32 v13, v4, v5
	v_mul_lo_u32 v4, v12, s49
	v_lshl_add_u32 v4, v13, 4, v4
	ds_read_b128 v[4:7], v4
	s_waitcnt lgkmcnt(1)
	global_store_dwordx4 v[10:11], v[0:3], off
	s_nop 1
	v_lshlrev_b32_e32 v0, 3, v13
	v_ashrrev_i32_e32 v1, 31, v0
	v_mad_i64_i32 v[2:3], s[14:15], v12, s50, v[8:9]
	v_lshl_add_u64 v[0:1], v[0:1], 1, v[2:3]
	s_waitcnt lgkmcnt(0)
	global_store_dwordx4 v[0:1], v[4:7], off
	s_cbranch_scc0 .LBB0_1073

; __device__ void phase_inproj(const Params& p, int layer, char* smem) {
;     ...
;     if (cb >= 26 && cb <= 29) {
;       float mx = 0.f;
; #pragma unroll
;       for (int m = 0; m < 4; ++m)
; #pragma unroll
;         for (int j = 0; j < 4; ++j) {
;           float ss = 0.f;
; #pragma unroll
;           for (int n = 0; n < 4; ++n) ss += acc[m][n][j] * acc[m][n][j];
;           ss += __shfl_xor(ss, 1);
;           ss += __shfl_xor(ss, 2);
;           ss += __shfl_xor(ss, 4);
;           ss += __shfl_xor(ss, 8);
;           mx = fmaxf(mx, ss);
;         }
.LBB0_1070:
	s_sub_i32 s12, s16, 26
	s_cmp_gt_u32 s12, 3
	s_cbranch_scc1 .LBB0_1065
	v_and_b32_e32 v65, 64, v129
	v_xor_b32_e32 v64, 1, v129
	v_add_u32_e32 v65, 64, v65
	v_mul_f32_e32 v66, v44, v44
	v_mul_f32_e32 v71, v45, v45
	v_cmp_lt_i32_e32 vcc, v64, v65
	v_fmac_f32_e32 v66, v40, v40
	v_fmac_f32_e32 v71, v41, v41
	v_mul_f32_e32 v73, v46, v46
	v_mul_f32_e32 v75, v47, v47
	v_cndmask_b32_e32 v64, v129, v64, vcc
	v_fmac_f32_e32 v66, v36, v36
	v_fmac_f32_e32 v71, v37, v37
	v_fmac_f32_e32 v73, v42, v42
	v_fmac_f32_e32 v75, v43, v43
	v_lshlrev_b32_e32 v64, 2, v64
	v_fmac_f32_e32 v66, v32, v32
	v_fmac_f32_e32 v71, v33, v33
	v_fmac_f32_e32 v73, v38, v38
	v_fmac_f32_e32 v75, v39, v39
	ds_bpermute_b32 v67, v64, v66
	ds_bpermute_b32 v72, v64, v71
	v_fmac_f32_e32 v73, v34, v34
	v_fmac_f32_e32 v75, v35, v35
	ds_bpermute_b32 v74, v64, v73
	ds_bpermute_b32 v76, v64, v75
	v_xor_b32_e32 v68, 2, v129
	v_cmp_lt_i32_e32 vcc, v68, v65
	s_waitcnt lgkmcnt(3)
	v_add_f32_e32 v66, v66, v67
	s_waitcnt lgkmcnt(2)
	v_add_f32_e32 v71, v71, v72
	v_cndmask_b32_e32 v68, v129, v68, vcc
	v_lshlrev_b32_e32 v68, 2, v68
	ds_bpermute_b32 v67, v68, v66
	ds_bpermute_b32 v72, v68, v71
	s_waitcnt lgkmcnt(3)
	v_add_f32_e32 v73, v73, v74
	s_waitcnt lgkmcnt(2)
	v_add_f32_e32 v75, v75, v76
	ds_bpermute_b32 v74, v68, v73
	ds_bpermute_b32 v76, v68, v75
	v_xor_b32_e32 v69, 4, v129
	v_cmp_lt_i32_e32 vcc, v69, v65
	s_waitcnt lgkmcnt(3)
	v_add_f32_e32 v66, v66, v67
	s_waitcnt lgkmcnt(2)
	v_add_f32_e32 v71, v71, v72
	v_cndmask_b32_e32 v69, v129, v69, vcc
	v_lshlrev_b32_e32 v69, 2, v69
	ds_bpermute_b32 v67, v69, v66
	ds_bpermute_b32 v72, v69, v71
	s_waitcnt lgkmcnt(3)
	v_add_f32_e32 v73, v73, v74
	s_waitcnt lgkmcnt(2)
	v_add_f32_e32 v75, v75, v76
	ds_bpermute_b32 v74, v69, v73
	ds_bpermute_b32 v76, v69, v75
	v_xor_b32_e32 v70, 8, v129
	v_cmp_lt_i32_e32 vcc, v70, v65
	s_waitcnt lgkmcnt(3)
	v_add_f32_e32 v66, v66, v67
	s_waitcnt lgkmcnt(2)
	v_add_f32_e32 v71, v71, v72
	v_cndmask_b32_e32 v70, v129, v70, vcc
	v_lshlrev_b32_e32 v70, 2, v70
	ds_bpermute_b32 v67, v70, v66
	ds_bpermute_b32 v72, v70, v71
	s_waitcnt lgkmcnt(3)
	v_add_f32_e32 v73, v73, v74
	s_waitcnt lgkmcnt(2)
	v_add_f32_e32 v75, v75, v76
	ds_bpermute_b32 v74, v70, v73
	ds_bpermute_b32 v76, v70, v75
	s_waitcnt lgkmcnt(3)
	v_add_f32_e32 v66, v66, v67
	s_waitcnt lgkmcnt(2)
	v_add_f32_e32 v67, v71, v72
	v_max3_f32 v66, v66, 0, v67
	s_waitcnt lgkmcnt(1)
	v_add_f32_e32 v67, v73, v74
	s_waitcnt lgkmcnt(0)
	v_add_f32_e32 v71, v75, v76
	v_max3_f32 v66, v66, v67, v71
	v_mul_f32_e32 v67, v28, v28
	v_mul_f32_e32 v72, v29, v29
	v_fmac_f32_e32 v67, v24, v24
	v_fmac_f32_e32 v72, v25, v25
	v_mul_f32_e32 v74, v30, v30
	v_fmac_f32_e32 v67, v20, v20
	v_fmac_f32_e32 v72, v21, v21
	v_fmac_f32_e32 v74, v26, v26
	v_fmac_f32_e32 v67, v16, v16
	v_fmac_f32_e32 v72, v17, v17
	v_fmac_f32_e32 v74, v22, v22
	ds_bpermute_b32 v71, v64, v67
	ds_bpermute_b32 v73, v64, v72
	v_fmac_f32_e32 v74, v18, v18
	ds_bpermute_b32 v75, v64, v74
	v_mul_f32_e32 v76, v31, v31
	s_waitcnt lgkmcnt(2)
	v_add_f32_e32 v67, v67, v71
	s_waitcnt lgkmcnt(1)
	v_add_f32_e32 v72, v72, v73
	ds_bpermute_b32 v71, v68, v67
	ds_bpermute_b32 v73, v68, v72
	s_waitcnt lgkmcnt(2)
	v_add_f32_e32 v74, v74, v75
	ds_bpermute_b32 v75, v68, v74
	v_fmac_f32_e32 v76, v27, v27
	s_waitcnt lgkmcnt(2)
	v_add_f32_e32 v67, v67, v71
	s_waitcnt lgkmcnt(1)
	v_add_f32_e32 v72, v72, v73
	ds_bpermute_b32 v71, v69, v67
	ds_bpermute_b32 v73, v69, v72
	s_waitcnt lgkmcnt(2)
	v_add_f32_e32 v74, v74, v75
	ds_bpermute_b32 v75, v69, v74
	v_fmac_f32_e32 v76, v23, v23
	s_waitcnt lgkmcnt(2)
	v_add_f32_e32 v67, v67, v71
	s_waitcnt lgkmcnt(1)
	v_add_f32_e32 v72, v72, v73
	ds_bpermute_b32 v71, v70, v67
	ds_bpermute_b32 v73, v70, v72
	s_waitcnt lgkmcnt(2)
	v_add_f32_e32 v74, v74, v75
	ds_bpermute_b32 v75, v70, v74
	v_fmac_f32_e32 v76, v19, v19
	ds_bpermute_b32 v77, v64, v76
	s_waitcnt lgkmcnt(3)
	v_add_f32_e32 v67, v67, v71
	s_waitcnt lgkmcnt(2)
	v_add_f32_e32 v71, v72, v73
	v_max3_f32 v66, v66, v67, v71
	s_waitcnt lgkmcnt(1)
	v_add_f32_e32 v67, v74, v75
	v_mul_f32_e32 v73, v12, v12
	v_mul_f32_e32 v75, v13, v13
	v_fmac_f32_e32 v73, v8, v8
	v_fmac_f32_e32 v75, v9, v9
	s_waitcnt lgkmcnt(0)
	v_add_f32_e32 v71, v76, v77
	v_fmac_f32_e32 v73, v4, v4
	v_fmac_f32_e32 v75, v5, v5
	ds_bpermute_b32 v72, v68, v71
	v_fmac_f32_e32 v73, v0, v0
	v_fmac_f32_e32 v75, v1, v1
	ds_bpermute_b32 v74, v64, v73
	ds_bpermute_b32 v76, v64, v75
	s_waitcnt lgkmcnt(2)
	v_add_f32_e32 v71, v71, v72
	ds_bpermute_b32 v72, v69, v71
	s_waitcnt lgkmcnt(2)
	v_add_f32_e32 v73, v73, v74
	s_waitcnt lgkmcnt(1)
; __device__ void phase_inproj(const Params& p, int layer, char* smem) {
;     ...
;           ss += __shfl_xor(ss, 1);
;           ss += __shfl_xor(ss, 2);
;           ss += __shfl_xor(ss, 4);
;           ss += __shfl_xor(ss, 8);
;           mx = fmaxf(mx, ss);
;         }
;       mx = fmaxf(mx, __shfl_xor(mx, 16));
;       mx = fmaxf(mx, __shfl_xor(mx, 32));
;       if (lane == 0) {
;         unsigned* km = reinterpret_cast<unsigned*>(wsb(p) + OFF_MISC) + 64 + layer * 16 + (rb >> 7) * 8 + (cb - 26) * 2 + wc;
;         atomicMax(km, __float_as_uint(mx));
;       }
	v_add_f32_e32 v75, v75, v76
	ds_bpermute_b32 v74, v68, v73
	ds_bpermute_b32 v76, v68, v75
	s_waitcnt lgkmcnt(2)
	v_add_f32_e32 v71, v71, v72
	ds_bpermute_b32 v72, v70, v71
	s_waitcnt lgkmcnt(2)
	v_add_f32_e32 v73, v73, v74
	s_waitcnt lgkmcnt(1)
	v_add_f32_e32 v75, v75, v76
	ds_bpermute_b32 v74, v69, v73
	ds_bpermute_b32 v76, v69, v75
	s_waitcnt lgkmcnt(2)
	v_add_f32_e32 v71, v71, v72
	v_max3_f32 v66, v66, v67, v71
	s_waitcnt lgkmcnt(1)
	v_add_f32_e32 v67, v73, v74
	s_waitcnt lgkmcnt(0)
	v_add_f32_e32 v72, v75, v76
	v_mul_f32_e32 v74, v14, v14
	v_mul_f32_e32 v76, v15, v15
	v_fmac_f32_e32 v74, v10, v10
	v_fmac_f32_e32 v76, v11, v11
	v_fmac_f32_e32 v74, v6, v6
	v_fmac_f32_e32 v76, v7, v7
	v_fmac_f32_e32 v74, v2, v2
	v_fmac_f32_e32 v76, v3, v3
	ds_bpermute_b32 v71, v70, v67
	ds_bpermute_b32 v73, v70, v72
	ds_bpermute_b32 v75, v64, v74
	ds_bpermute_b32 v77, v64, v76
	s_waitcnt lgkmcnt(3)
	v_add_f32_e32 v67, v67, v71
	s_waitcnt lgkmcnt(2)
	v_add_f32_e32 v71, v72, v73
	s_waitcnt lgkmcnt(1)
	v_add_f32_e32 v72, v74, v75
	s_waitcnt lgkmcnt(0)
	v_add_f32_e32 v74, v76, v77
	v_mul_f32_e32 v76, v60, v60
	v_fmac_f32_e32 v76, v56, v56
	v_fmac_f32_e32 v76, v52, v52
	ds_bpermute_b32 v73, v68, v72
	ds_bpermute_b32 v75, v68, v74
	v_fmac_f32_e32 v76, v48, v48
	ds_bpermute_b32 v77, v64, v76
	v_max3_f32 v66, v66, v67, v71
	s_waitcnt lgkmcnt(2)
	v_add_f32_e32 v72, v72, v73
	s_waitcnt lgkmcnt(1)
	v_add_f32_e32 v74, v74, v75
	ds_bpermute_b32 v73, v69, v72
	ds_bpermute_b32 v75, v69, v74
	s_waitcnt lgkmcnt(2)
	v_add_f32_e32 v76, v76, v77
	ds_bpermute_b32 v77, v68, v76
	s_waitcnt lgkmcnt(2)
	v_add_f32_e32 v72, v72, v73
	s_waitcnt lgkmcnt(1)
	v_add_f32_e32 v74, v74, v75
	ds_bpermute_b32 v73, v70, v72
	ds_bpermute_b32 v75, v70, v74
	s_waitcnt lgkmcnt(2)
	v_add_f32_e32 v76, v76, v77
	ds_bpermute_b32 v77, v69, v76
	s_waitcnt lgkmcnt(2)
	v_add_f32_e32 v67, v72, v73
	s_waitcnt lgkmcnt(1)
	v_add_f32_e32 v71, v74, v75
	v_mul_f32_e32 v72, v61, v61
	v_max3_f32 v66, v66, v67, v71
	s_waitcnt lgkmcnt(0)
	v_add_f32_e32 v67, v76, v77
	v_fmac_f32_e32 v72, v57, v57
	v_mul_f32_e32 v74, v62, v62
	v_mul_f32_e32 v76, v63, v63
	v_fmac_f32_e32 v72, v53, v53
	v_fmac_f32_e32 v74, v58, v58
	v_fmac_f32_e32 v76, v59, v59
	v_fmac_f32_e32 v72, v49, v49
	v_fmac_f32_e32 v74, v54, v54
	v_fmac_f32_e32 v76, v55, v55
	ds_bpermute_b32 v73, v64, v72
	v_fmac_f32_e32 v74, v50, v50
	v_fmac_f32_e32 v76, v51, v51
	ds_bpermute_b32 v75, v64, v74
	ds_bpermute_b32 v64, v64, v76
	s_waitcnt lgkmcnt(2)
	v_add_f32_e32 v72, v72, v73
	ds_bpermute_b32 v73, v68, v72
	ds_bpermute_b32 v71, v70, v67
	s_waitcnt lgkmcnt(3)
	v_add_f32_e32 v74, v74, v75
	s_waitcnt lgkmcnt(2)
	v_add_f32_e32 v64, v76, v64
	ds_bpermute_b32 v75, v68, v74
	ds_bpermute_b32 v68, v68, v64
	s_waitcnt lgkmcnt(3)
	v_add_f32_e32 v72, v72, v73
	ds_bpermute_b32 v73, v69, v72
	s_waitcnt lgkmcnt(3)
	v_add_f32_e32 v67, v67, v71
	s_waitcnt lgkmcnt(2)
	v_add_f32_e32 v74, v74, v75
	s_waitcnt lgkmcnt(1)
	v_add_f32_e32 v64, v64, v68
	ds_bpermute_b32 v75, v69, v74
	ds_bpermute_b32 v68, v69, v64
	s_waitcnt lgkmcnt(2)
	v_add_f32_e32 v69, v72, v73
	ds_bpermute_b32 v72, v70, v69
	s_waitcnt lgkmcnt(2)
	v_add_f32_e32 v73, v74, v75
	s_waitcnt lgkmcnt(1)
	v_add_f32_e32 v64, v64, v68
	ds_bpermute_b32 v74, v70, v73
	ds_bpermute_b32 v68, v70, v64
	s_waitcnt lgkmcnt(2)
	v_add_f32_e32 v69, v69, v72
	v_max3_f32 v66, v66, v67, v69
	s_waitcnt lgkmcnt(1)
	v_add_f32_e32 v67, v73, v74
	s_waitcnt lgkmcnt(0)
	v_add_f32_e32 v64, v64, v68
	v_max3_f32 v64, v66, v67, v64
	v_xor_b32_e32 v66, 16, v129
	v_cmp_lt_i32_e32 vcc, v66, v65
	s_nop 1
	v_cndmask_b32_e32 v66, v129, v66, vcc
	v_lshlrev_b32_e32 v66, 2, v66
	ds_bpermute_b32 v66, v66, v64
	s_waitcnt lgkmcnt(0)
	v_max_f32_e32 v64, v64, v66
	v_xor_b32_e32 v66, 32, v129
	v_cmp_lt_i32_e32 vcc, v66, v65
	s_nop 1
	v_cndmask_b32_e32 v65, v129, v66, vcc
	v_lshlrev_b32_e32 v65, 2, v65
	ds_bpermute_b32 v65, v65, v64
	s_and_saveexec_b64 s[20:21], s[6:7]
	s_cbranch_execz .LBB0_1064
	s_waitcnt lgkmcnt(0)
	v_max_f32_e32 v66, v64, v65
	v_mov_b32_e32 v64, v117
	v_mov_b32_e32 v119, v117
	v_readfirstlane_b32 s12, v64
	s_ashr_i32 s15, s12, 31
	s_add_u32 s12, s28, s12
	s_addc_u32 s15, s29, s15
	s_ashr_i32 s17, s14, 4
	s_and_b32 s22, s17, -8
	s_ashr_i32 s23, s22, 31
	s_lshl_b64 s[22:23], s[22:23], 2
	s_add_u32 s17, s12, s22
	s_addc_u32 s15, s15, s23
	s_lshl_b32 s12, s16, 1
	s_lshl_b64 s[22:23], s[12:13], 2
	s_add_u32 s22, s17, s22
	s_addc_u32 s23, s15, s23
	v_lshl_add_u64 v[64:65], s[22:23], 0, v[118:119]
	v_add_co_u32_e32 v64, vcc, 0x1e8a4000, v64
	s_nop 1
	v_addc_co_u32_e32 v65, vcc, 0, v65, vcc
	global_atomic_umax v[64:65], v66, off offset:2288
	s_branch .LBB0_1064

; template <int DH, int MODE>
; __device__ void attn_item(const Params& p, int layer, int b, int blk, int head, char* smem) {
;     ...
;     constexpr int NCH = 128 * CPR / 256;
;     float* Of = reinterpret_cast<float*>(smem);
;     uint4 gt[NCH];
; #pragma unroll
;     for (int i = 0; i < NCH; ++i) {
;       int q = tid + 256 * i, r = q / CPR, c = (q % CPR) * 8;
;       gt[i] = *reinterpret_cast<const uint4*>(P + (tq0 + r) * NP + gcol + c);
;     }
;     float lis[2][4];
; #pragma unroll
;     for (int m = 0; m < 2; ++m)
; #pragma unroll
;       for (int j = 0; j < 4; ++j) lis[m][j] = (MODE == 0) ? linv_s[wid * 32 + m * 16 + fq * 4 + j] : 1.f;
;     if (MODE == 0) __syncthreads();
; #pragma unroll
;     for (int m = 0; m < 2; ++m)
; #pragma unroll
;       for (int j = 0; j < 4; ++j) {
;         int r = wid * 32 + m * 16 + fq * 4 + j;
; #pragma unroll
;         for (int n = 0; n < NDT; ++n) Of[r * OST + n * 16 + fr] = o[m][n][j] * lis[m][j];
;       }
.LBB0_1112:
	s_ashr_i32 s7, s79, 31
	s_add_u32 s6, s28, s79
	s_addc_u32 s7, s29, s7
	s_lshl_b32 s8, s76, 1
	s_add_u32 s10, s42, s8
	s_addc_u32 s11, s43, 0
	v_lshl_add_u64 v[2:3], s[12:13], 0, v[134:135]
	v_mov_b64_e32 v[4:5], s[10:11]
	v_mad_u64_u32 v[0:1], s[10:11], v2, s39, v[4:5]
	v_mad_i32_i24 v1, v3, s39, v1
	s_waitcnt vmcnt(12)
	v_lshl_add_u64 v[76:77], v[0:1], 0, v[138:139]
	v_add_u32_e32 v0, 0x100, v161
	v_ashrrev_i32_e32 v1, 31, v0
	v_lshrrev_b32_e32 v1, 28, v1
	v_add_u32_e32 v1, v0, v1
	v_ashrrev_i32_e32 v8, 4, v1
	v_and_b32_e32 v1, -16, v1
	s_waitcnt vmcnt(5)
	v_sub_u32_e32 v99, v0, v1
	v_lshlrev_b32_e32 v0, 3, v99
	v_ashrrev_i32_e32 v1, 31, v0
	s_waitcnt vmcnt(3)
	v_lshlrev_b64 v[92:93], 1, v[0:1]
	v_add_u32_e32 v0, 0x200, v161
	v_ashrrev_i32_e32 v1, 31, v0
	v_lshrrev_b32_e32 v1, 28, v1
	v_add_u32_e32 v1, v0, v1
	v_ashrrev_i32_e32 v9, 31, v8
	v_ashrrev_i32_e32 v94, 4, v1
	v_and_b32_e32 v1, -16, v1
	v_lshl_add_u64 v[10:11], s[12:13], 0, v[8:9]
	v_sub_u32_e32 v9, v0, v1
	v_lshlrev_b32_e32 v0, 3, v9
	v_ashrrev_i32_e32 v1, 31, v0
	v_lshlrev_b64 v[100:101], 1, v[0:1]
	v_add_u32_e32 v0, 0x300, v161
	v_ashrrev_i32_e32 v1, 31, v0
	v_lshrrev_b32_e32 v1, 28, v1
	v_add_u32_e32 v1, v0, v1
	v_ashrrev_i32_e32 v102, 4, v1
	v_and_b32_e32 v1, -16, v1
	v_sub_u32_e32 v128, v0, v1
	v_lshlrev_b32_e32 v0, 3, v128
	v_ashrrev_i32_e32 v1, 31, v0
	s_waitcnt vmcnt(0)
	v_lshlrev_b64 v[106:107], 1, v[0:1]
	v_add_u32_e32 v0, 0x400, v161
	v_ashrrev_i32_e32 v1, 31, v0
	v_lshrrev_b32_e32 v1, 28, v1
	v_add_u32_e32 v1, v0, v1
	v_ashrrev_i32_e32 v103, 31, v102
	v_ashrrev_i32_e32 v108, 4, v1
	v_and_b32_e32 v1, -16, v1
	v_lshl_add_u64 v[104:105], s[12:13], 0, v[102:103]
	v_sub_u32_e32 v103, v0, v1
	v_lshlrev_b32_e32 v0, 3, v103
	v_ashrrev_i32_e32 v1, 31, v0
	v_lshlrev_b64 v[112:113], 1, v[0:1]
	v_add_u32_e32 v0, 0x500, v161
	v_ashrrev_i32_e32 v1, 31, v0
	v_lshrrev_b32_e32 v1, 28, v1
	v_add_u32_e32 v1, v0, v1
	v_ashrrev_i32_e32 v109, 31, v108
	v_ashrrev_i32_e32 v114, 4, v1
	v_and_b32_e32 v1, -16, v1
	v_mad_u64_u32 v[6:7], s[10:11], v10, s39, v[4:5]
	v_ashrrev_i32_e32 v95, 31, v94
	v_lshl_add_u64 v[110:111], s[12:13], 0, v[108:109]
	v_sub_u32_e32 v109, v0, v1
	v_mad_i32_i24 v7, v11, s39, v7
	v_lshl_add_u64 v[96:97], s[12:13], 0, v[94:95]
	v_lshlrev_b32_e32 v0, 3, v109
	v_lshl_add_u64 v[78:79], v[6:7], 0, v[92:93]
	v_mad_u64_u32 v[6:7], s[10:11], v96, s39, v[4:5]
	v_ashrrev_i32_e32 v1, 31, v0
	v_mad_i32_i24 v7, v97, s39, v7
	v_lshlrev_b64 v[118:119], 1, v[0:1]
	v_add_u32_e32 v0, 0x600, v161
	v_lshl_add_u64 v[80:81], v[6:7], 0, v[100:101]
	v_mad_u64_u32 v[6:7], s[10:11], v104, s39, v[4:5]
	v_ashrrev_i32_e32 v1, 31, v0
	v_mad_i32_i24 v7, v105, s39, v7
	v_lshrrev_b32_e32 v1, 28, v1
	v_lshl_add_u64 v[82:83], v[6:7], 0, v[106:107]
	v_mad_u64_u32 v[6:7], s[10:11], v110, s39, v[4:5]
	v_ashrrev_i32_e32 v115, 31, v114
	v_add_u32_e32 v1, v0, v1
	v_mad_i32_i24 v7, v111, s39, v7
	v_lshl_add_u64 v[116:117], s[12:13], 0, v[114:115]
	v_ashrrev_i32_e32 v120, 4, v1
	v_and_b32_e32 v1, -16, v1
	v_lshl_add_u64 v[84:85], v[6:7], 0, v[112:113]
	v_mad_u64_u32 v[6:7], s[10:11], v116, s39, v[4:5]
	v_sub_u32_e32 v115, v0, v1
	v_ashrrev_i32_e32 v121, 31, v120
	v_mad_i32_i24 v7, v117, s39, v7
	v_lshlrev_b32_e32 v0, 3, v115
	v_lshl_add_u64 v[122:123], s[12:13], 0, v[120:121]
	v_lshl_add_u64 v[86:87], v[6:7], 0, v[118:119]
	v_mad_u64_u32 v[6:7], s[10:11], v122, s39, v[4:5]
	v_ashrrev_i32_e32 v1, 31, v0
	v_mad_i32_i24 v7, v123, s39, v7
	v_lshlrev_b64 v[124:125], 1, v[0:1]
	v_lshl_add_u64 v[0:1], v[6:7], 0, v[124:125]
	v_add_u32_e32 v6, 0x700, v161
	v_ashrrev_i32_e32 v7, 31, v6
	v_lshrrev_b32_e32 v7, 28, v7
	v_add_u32_e32 v7, v6, v7
	v_ashrrev_i32_e32 v126, 4, v7
	v_and_b32_e32 v7, -16, v7
	v_sub_u32_e32 v121, v6, v7
	v_lshlrev_b32_e32 v6, 3, v121
	v_ashrrev_i32_e32 v127, 31, v126
	v_lshl_add_u64 v[88:89], s[12:13], 0, v[126:127]
	v_ashrrev_i32_e32 v7, 31, v6
	v_mad_u64_u32 v[4:5], s[10:11], v88, s39, v[4:5]
	v_lshlrev_b64 v[90:91], 1, v[6:7]
	v_lshl_or_b32 v6, v137, 2, v130
	v_mad_i32_i24 v5, v89, s39, v5
	v_mul_lo_u32 v6, v6, s55
	v_lshl_add_u64 v[4:5], v[4:5], 0, v[90:91]
	v_lshl_add_u32 v95, v162, 2, v6
	s_barrier
	ds_write2_b32 v95, v12, v48 offset1:16
	ds_write2_b32 v95, v52, v56 offset0:32 offset1:48
	ds_write2_b32 v95, v60, v64 offset0:64 offset1:80
	ds_write2_b32 v95, v68, v72 offset0:96 offset1:112
	ds_write2_b32 v95, v13, v49 offset0:132 offset1:148
	ds_write2_b32 v95, v53, v57 offset0:164 offset1:180
	ds_write2_b32 v95, v61, v65 offset0:196 offset1:212
	ds_write2_b32 v95, v69, v73 offset0:228 offset1:244
	v_add_u32_e32 v12, 0x400, v95
	v_add_co_u32_e32 v4, vcc, s73, v4
	ds_write2_b32 v12, v14, v50 offset0:8 offset1:24
	ds_write2_b32 v12, v54, v58 offset0:40 offset1:56
	v_addc_co_u32_e32 v5, vcc, 0, v5, vcc
	global_load_dwordx4 v[4:7], v[4:5], off offset:512
	ds_write2_b32 v12, v62, v66 offset0:72 offset1:88
	ds_write2_b32 v12, v70, v74 offset0:104 offset1:120
	ds_write2_b32 v12, v15, v51 offset0:140 offset1:156
	ds_write2_b32 v12, v55, v59 offset0:172 offset1:188
	ds_write2_b32 v12, v63, v67 offset0:204 offset1:220
	ds_write2_b32 v12, v71, v75 offset0:236 offset1:252
	v_add_u32_e32 v12, 0x2000, v95
	ds_write2_b32 v12, v16, v20 offset0:64 offset1:80
	ds_write2_b32 v12, v24, v36 offset0:96 offset1:112
	ds_write2_b32 v12, v28, v40 offset0:128 offset1:144
	ds_write2_b32 v12, v44, v32 offset0:160 offset1:176
	ds_write2_b32 v12, v17, v21 offset0:196 offset1:212
	ds_write2_b32 v12, v25, v37 offset0:228 offset1:244
	v_add_u32_e32 v12, 0x2400, v95
	s_add_u32 s6, s6, s8
	ds_write2_b32 v12, v29, v41 offset0:4 offset1:20
	ds_write2_b32 v12, v45, v33 offset0:36 offset1:52
; __device__ __forceinline__ unsigned pack2(float a, float b) { return (unsigned)f2bf(a) | ((unsigned)f2bf(b) << 16); }
; __device__ __forceinline__ float bflo(unsigned w) { return __uint_as_float(w << 16); }
; __device__ __forceinline__ float bfhi(unsigned w) { return __uint_as_float(w & 0xffff0000u); }
; __device__ __forceinline__ float silu_f(float g) { return g / (1.f + __expf(-g)); }
; template <int DH, int MODE>
; __device__ void attn_item(const Params& p, int layer, int b, int blk, int head, char* smem) {
;     ...
; #pragma unroll
;     for (int m = 0; m < 2; ++m)
; #pragma unroll
;       for (int j = 0; j < 4; ++j) {
;         int r = wid * 32 + m * 16 + fq * 4 + j;
; #pragma unroll
;         for (int n = 0; n < NDT; ++n) Of[r * OST + n * 16 + fr] = o[m][n][j] * lis[m][j];
;       }
;     __syncthreads();
; #pragma unroll
;     for (int i = 0; i < NCH; ++i) {
;       int q = tid + 256 * i, r = q / CPR, c = (q % CPR) * 8;
;       float4 m0 = *reinterpret_cast<const float4*>(Of + r * OST + c);
;       float4 m1 = *reinterpret_cast<const float4*>(Of + r * OST + c + 4);
;       float mm[8] = {m0.x, m0.y, m0.z, m0.w, m1.x, m1.y, m1.z, m1.w};
;       unsigned gw[4] = {gt[i].x, gt[i].y, gt[i].z, gt[i].w};
;       unsigned ow[4];
; #pragma unroll
;       for (int e = 0; e < 4; ++e)
;         ow[e] = pack2(mm[2 * e] * silu_f(bflo(gw[e])), mm[2 * e + 1] * silu_f(bfhi(gw[e])));
	ds_write2_b32 v12, v18, v22 offset0:72 offset1:88
	ds_write2_b32 v12, v26, v38 offset0:104 offset1:120
	ds_write2_b32 v12, v30, v42 offset0:136 offset1:152
	ds_write2_b32 v12, v46, v34 offset0:168 offset1:184
	ds_write2_b32 v12, v19, v23 offset0:204 offset1:220
	ds_write2_b32 v12, v27, v39 offset0:236 offset1:252
	v_add_u32_e32 v12, 0x2800, v95
	s_addc_u32 s7, s7, 0
	ds_write2_b32 v12, v31, v43 offset0:12 offset1:28
	ds_write2_b32 v12, v47, v35 offset0:44 offset1:60
	v_mul_lo_u32 v12, v134, s55
	v_mov_b64_e32 v[14:15], s[6:7]
	v_lshl_add_u32 v98, v136, 2, v12
	v_mad_u64_u32 v[12:13], s[6:7], v2, s63, v[14:15]
	v_mul_lo_u32 v2, v8, s55
	v_mad_i32_i24 v13, v3, s63, v13
	v_lshl_add_u32 v95, v99, 5, v2
	v_mad_u64_u32 v[2:3], s[6:7], v10, s63, v[14:15]
	v_mad_i32_i24 v3, v11, s63, v3
	v_lshl_add_u64 v[26:27], v[2:3], 0, v[92:93]
	v_mul_lo_u32 v2, v94, s55
	v_lshl_add_u32 v93, v9, 5, v2
	v_mad_u64_u32 v[2:3], s[6:7], v96, s63, v[14:15]
	v_mad_i32_i24 v3, v97, s63, v3
	v_lshl_add_u64 v[20:21], v[2:3], 0, v[100:101]
	v_mul_lo_u32 v2, v102, s55
	v_lshl_add_u32 v92, v128, 5, v2
	v_mad_u64_u32 v[2:3], s[6:7], v104, s63, v[14:15]
	v_mad_i32_i24 v3, v105, s63, v3
	v_lshl_add_u64 v[16:17], v[2:3], 0, v[106:107]
	v_mul_lo_u32 v2, v108, s55
	v_lshl_add_u32 v75, v103, 5, v2
	v_mad_u64_u32 v[2:3], s[6:7], v110, s63, v[14:15]
	v_mad_i32_i24 v3, v111, s63, v3
	v_lshl_add_u64 v[30:31], v[12:13], 0, v[138:139]
	v_lshl_add_u64 v[12:13], v[2:3], 0, v[112:113]
	v_mul_lo_u32 v2, v114, s55
	v_lshl_add_u32 v74, v109, 5, v2
	v_mad_u64_u32 v[2:3], s[6:7], v116, s63, v[14:15]
	v_mad_i32_i24 v3, v117, s63, v3
	v_lshl_add_u64 v[10:11], v[2:3], 0, v[118:119]
	v_mul_lo_u32 v2, v120, s55
	v_lshl_add_u32 v73, v115, 5, v2
	v_mad_u64_u32 v[2:3], s[6:7], v122, s63, v[14:15]
	v_mad_i32_i24 v3, v123, s63, v3
	v_add_co_u32_e32 v0, vcc, s73, v0
	v_lshl_add_u64 v[8:9], v[2:3], 0, v[124:125]
	v_mul_lo_u32 v2, v126, s55
	v_addc_co_u32_e32 v1, vcc, 0, v1, vcc
	v_lshl_add_u32 v72, v121, 5, v2
	global_load_dwordx4 v[0:3], v[0:1], off offset:512
	v_mad_u64_u32 v[14:15], s[6:7], v88, s63, v[14:15]
	v_mad_i32_i24 v15, v89, s63, v15
	v_lshl_add_u64 v[14:15], v[14:15], 0, v[90:91]
	s_waitcnt vmcnt(1)
	v_lshlrev_b32_e32 v22, 16, v5
	v_lshlrev_b32_e32 v23, 16, v4
	v_mul_f32_e32 v18, 0xbfb8aa3b, v23
	v_mul_f32_e32 v19, 0xbfb8aa3b, v22
	v_exp_f32_e32 v18, v18
	v_exp_f32_e32 v19, v19
	v_and_b32_e32 v24, 0xffff0000, v5
	v_and_b32_e32 v28, 0xffff0000, v4
	v_mul_f32_e32 v4, 0xbfb8aa3b, v28
	v_pk_add_f32 v[18:19], v[18:19], 1.0 op_sel_hi:[1,0]
	v_exp_f32_e32 v4, v4
	v_and_b32_e32 v34, 0xffff0000, v6
	v_rcp_f32_e32 v19, v19
	s_nop 0
	v_mul_f32_e32 v19, v22, v19
	v_mul_f32_e32 v5, 0xbfb8aa3b, v24
	v_exp_f32_e32 v5, v5
	s_nop 0
	v_pk_add_f32 v[4:5], v[4:5], 1.0 op_sel_hi:[1,0]
	v_rcp_f32_e32 v18, v18
	s_nop 0
	v_mul_f32_e32 v18, v23, v18
	v_lshlrev_b32_e32 v33, 16, v6
	v_rcp_f32_e32 v23, v5
	s_nop 0
	v_mul_f32_e32 v23, v24, v23
	v_lshlrev_b32_e32 v32, 16, v7
	v_mul_f32_e32 v24, 0xbfb8aa3b, v33
	v_mul_f32_e32 v25, 0xbfb8aa3b, v32
	v_exp_f32_e32 v24, v24
	v_exp_f32_e32 v25, v25
	v_rcp_f32_e32 v22, v4
	s_nop 0
	v_mul_f32_e32 v22, v28, v22
	v_and_b32_e32 v28, 0xffff0000, v7
	v_pk_add_f32 v[4:5], v[24:25], 1.0 op_sel_hi:[1,0]
	v_mul_f32_e32 v6, 0xbfb8aa3b, v34
	v_exp_f32_e32 v6, v6
	s_waitcnt vmcnt(0)
	v_lshlrev_b32_e32 v40, 16, v3
	v_lshlrev_b32_e32 v41, 16, v2
	v_rcp_f32_e32 v25, v5
	s_nop 0
	v_mul_f32_e32 v25, v32, v25
	v_mul_f32_e32 v7, 0xbfb8aa3b, v28
	v_exp_f32_e32 v7, v7
	s_nop 0
	v_pk_add_f32 v[6:7], v[6:7], 1.0 op_sel_hi:[1,0]
	v_rcp_f32_e32 v24, v4
	s_nop 0
	v_mul_f32_e32 v24, v33, v24
	v_rcp_f32_e32 v29, v7
	s_nop 0
	v_mul_f32_e32 v29, v28, v29
	v_lshlrev_b32_e32 v32, 16, v1
	v_lshlrev_b32_e32 v36, 16, v0
	v_mul_f32_e32 v4, 0xbfb8aa3b, v36
	v_mul_f32_e32 v5, 0xbfb8aa3b, v32
	v_exp_f32_e32 v4, v4
	v_exp_f32_e32 v5, v5
	v_rcp_f32_e32 v28, v6
	s_nop 0
	v_mul_f32_e32 v28, v34, v28
	v_and_b32_e32 v6, 0xffff0000, v1
	v_pk_add_f32 v[4:5], v[4:5], 1.0 op_sel_hi:[1,0]
	v_and_b32_e32 v34, 0xffff0000, v0
	v_mul_f32_e32 v0, 0xbfb8aa3b, v34
	v_exp_f32_e32 v0, v0
	v_and_b32_e32 v42, 0xffff0000, v3
	v_rcp_f32_e32 v33, v5
	s_nop 0
	v_mul_f32_e32 v33, v32, v33
	v_mul_f32_e32 v1, 0xbfb8aa3b, v6
	v_exp_f32_e32 v1, v1
	s_nop 0
	v_pk_add_f32 v[0:1], v[0:1], 1.0 op_sel_hi:[1,0]
	v_rcp_f32_e32 v32, v4
	s_nop 0
	v_mul_f32_e32 v32, v36, v32
	v_rcp_f32_e32 v35, v1
	s_nop 0
	v_mul_f32_e32 v35, v6, v35
	v_add_co_u32_e64 v4, s[6:7], s73, v86
	s_nop 0
	s_nop 0
	v_addc_co_u32_e64 v5, s[6:7], 0, v87, s[6:7]
	global_load_dwordx4 v[4:7], v[4:5], off offset:512
	v_mul_f32_e32 v36, 0xbfb8aa3b, v41
	v_mul_f32_e32 v37, 0xbfb8aa3b, v40
	v_exp_f32_e32 v36, v36
	v_exp_f32_e32 v37, v37
	v_rcp_f32_e32 v1, v0
	s_nop 0
	v_mul_f32_e32 v34, v34, v1
	v_and_b32_e32 v43, 0xffff0000, v2
	v_pk_add_f32 v[0:1], v[36:37], 1.0 op_sel_hi:[1,0]
	v_mul_f32_e32 v2, 0xbfb8aa3b, v43
	v_exp_f32_e32 v2, v2
	v_rcp_f32_e32 v37, v1
	s_nop 0
	v_mul_f32_e32 v37, v40, v37
	v_mul_f32_e32 v3, 0xbfb8aa3b, v42
	v_exp_f32_e32 v3, v3
	s_nop 0
	v_pk_add_f32 v[38:39], v[2:3], 1.0 op_sel_hi:[1,0]
	v_rcp_f32_e32 v36, v0
	s_nop 0
	v_mul_f32_e32 v36, v41, v36
	v_rcp_f32_e32 v39, v39
	s_nop 0
	v_mul_f32_e32 v39, v42, v39
	v_add_co_u32_e64 v0, s[6:7], s73, v84
	s_waitcnt vmcnt(0)
; __device__ __forceinline__ unsigned pack2(float a, float b) { return (unsigned)f2bf(a) | ((unsigned)f2bf(b) << 16); }
; __device__ __forceinline__ float bflo(unsigned w) { return __uint_as_float(w << 16); }
; __device__ __forceinline__ float bfhi(unsigned w) { return __uint_as_float(w & 0xffff0000u); }
; __device__ __forceinline__ float silu_f(float g) { return g / (1.f + __expf(-g)); }
; template <int DH, int MODE>
; __device__ void attn_item(const Params& p, int layer, int b, int blk, int head, char* smem) {
;     ...
;     for (int i = 0; i < NCH; ++i) {
;       int q = tid + 256 * i, r = q / CPR, c = (q % CPR) * 8;
;       float4 m0 = *reinterpret_cast<const float4*>(Of + r * OST + c);
;       float4 m1 = *reinterpret_cast<const float4*>(Of + r * OST + c + 4);
;       float mm[8] = {m0.x, m0.y, m0.z, m0.w, m1.x, m1.y, m1.z, m1.w};
;       unsigned gw[4] = {gt[i].x, gt[i].y, gt[i].z, gt[i].w};
;       unsigned ow[4];
; #pragma unroll
;       for (int e = 0; e < 4; ++e)
;         ow[e] = pack2(mm[2 * e] * silu_f(bflo(gw[e])), mm[2 * e + 1] * silu_f(bfhi(gw[e])));
	v_lshlrev_b32_e32 v46, 16, v5
	v_lshlrev_b32_e32 v47, 16, v4
	v_mul_f32_e32 v40, 0xbfb8aa3b, v47
	v_mul_f32_e32 v41, 0xbfb8aa3b, v46
	v_exp_f32_e32 v40, v40
	v_exp_f32_e32 v41, v41
	v_addc_co_u32_e64 v1, s[6:7], 0, v85, s[6:7]
	v_rcp_f32_e32 v38, v38
	s_nop 0
	v_mul_f32_e32 v38, v43, v38
	v_pk_add_f32 v[40:41], v[40:41], 1.0 op_sel_hi:[1,0]
	v_and_b32_e32 v42, 0xffff0000, v5
	global_load_dwordx4 v[0:3], v[0:1], off offset:512
	v_and_b32_e32 v48, 0xffff0000, v4
	v_mul_f32_e32 v4, 0xbfb8aa3b, v48
	v_rcp_f32_e32 v41, v41
	s_nop 0
	v_mul_f32_e32 v41, v46, v41
	v_exp_f32_e32 v4, v4
	v_mul_f32_e32 v5, 0xbfb8aa3b, v42
	v_exp_f32_e32 v5, v5
	s_nop 0
	v_pk_add_f32 v[4:5], v[4:5], 1.0 op_sel_hi:[1,0]
	v_rcp_f32_e32 v40, v40
	s_nop 0
	v_mul_f32_e32 v40, v47, v40
	v_lshlrev_b32_e32 v49, 16, v6
	v_rcp_f32_e32 v43, v5
	s_nop 0
	v_mul_f32_e32 v43, v42, v43
	v_lshlrev_b32_e32 v46, 16, v7
	v_mul_f32_e32 v44, 0xbfb8aa3b, v49
	v_mul_f32_e32 v45, 0xbfb8aa3b, v46
	v_exp_f32_e32 v44, v44
	v_exp_f32_e32 v45, v45
	v_rcp_f32_e32 v42, v4
	s_nop 0
	v_mul_f32_e32 v42, v48, v42
	v_and_b32_e32 v47, 0xffff0000, v7
	v_pk_add_f32 v[4:5], v[44:45], 1.0 op_sel_hi:[1,0]
	v_and_b32_e32 v48, 0xffff0000, v6
	v_mul_f32_e32 v6, 0xbfb8aa3b, v48
	v_exp_f32_e32 v6, v6
	v_rcp_f32_e32 v45, v5
	s_nop 0
	v_mul_f32_e32 v45, v46, v45
	v_mul_f32_e32 v7, 0xbfb8aa3b, v47
	v_exp_f32_e32 v7, v7
	s_nop 0
	v_pk_add_f32 v[6:7], v[6:7], 1.0 op_sel_hi:[1,0]
	v_rcp_f32_e32 v44, v4
	s_nop 0
	v_mul_f32_e32 v44, v49, v44
	v_rcp_f32_e32 v4, v7
	s_nop 0
	v_mul_f32_e32 v47, v47, v4
	s_waitcnt vmcnt(0)
	v_lshlrev_b32_e32 v50, 16, v1
	v_lshlrev_b32_e32 v51, 16, v0
	v_mul_f32_e32 v4, 0xbfb8aa3b, v51
	v_mul_f32_e32 v5, 0xbfb8aa3b, v50
	v_exp_f32_e32 v4, v4
	v_exp_f32_e32 v5, v5
	v_rcp_f32_e32 v46, v6
	s_nop 0
	v_mul_f32_e32 v46, v48, v46
	v_and_b32_e32 v6, 0xffff0000, v1
	v_pk_add_f32 v[4:5], v[4:5], 1.0 op_sel_hi:[1,0]
	v_and_b32_e32 v54, 0xffff0000, v0
	v_mul_f32_e32 v0, 0xbfb8aa3b, v54
	v_exp_f32_e32 v0, v0
	v_lshlrev_b32_e32 v58, 16, v2
	v_rcp_f32_e32 v49, v5
	s_nop 0
	v_mul_f32_e32 v49, v50, v49
	v_mul_f32_e32 v1, 0xbfb8aa3b, v6
	v_exp_f32_e32 v1, v1
	s_nop 0
	v_pk_add_f32 v[0:1], v[0:1], 1.0 op_sel_hi:[1,0]
	v_rcp_f32_e32 v48, v4
	s_nop 0
	v_mul_f32_e32 v48, v51, v48
	v_lshlrev_b32_e32 v57, 16, v3
	v_rcp_f32_e32 v51, v1
	s_nop 0
	v_mul_f32_e32 v51, v6, v51
	v_add_co_u32_e64 v4, s[6:7], s73, v82
	s_nop 0
	s_nop 0
	v_addc_co_u32_e64 v5, s[6:7], 0, v83, s[6:7]
	global_load_dwordx4 v[4:7], v[4:5], off offset:512
	v_mul_f32_e32 v50, 0xbfb8aa3b, v58
	v_exp_f32_e32 v52, v50
	v_mul_f32_e32 v50, 0xbfb8aa3b, v57
	v_exp_f32_e32 v53, v50
	v_rcp_f32_e32 v50, v0
	s_nop 0
	v_mul_f32_e32 v50, v54, v50
	v_and_b32_e32 v56, 0xffff0000, v3
	v_pk_add_f32 v[0:1], v[52:53], 1.0 op_sel_hi:[1,0]
	v_and_b32_e32 v59, 0xffff0000, v2
	v_mul_f32_e32 v2, 0xbfb8aa3b, v59
	v_exp_f32_e32 v2, v2
	v_rcp_f32_e32 v53, v1
	s_nop 0
	v_mul_f32_e32 v53, v57, v53
	v_mul_f32_e32 v3, 0xbfb8aa3b, v56
	v_exp_f32_e32 v3, v3
	s_nop 0
	v_pk_add_f32 v[54:55], v[2:3], 1.0 op_sel_hi:[1,0]
	v_rcp_f32_e32 v52, v0
	s_nop 0
	v_mul_f32_e32 v52, v58, v52
	v_rcp_f32_e32 v55, v55
	s_nop 0
	v_mul_f32_e32 v55, v56, v55
	v_add_co_u32_e64 v0, s[6:7], s73, v80
	s_waitcnt vmcnt(0)
	v_lshlrev_b32_e32 v62, 16, v5
	v_lshlrev_b32_e32 v63, 16, v4
	v_mul_f32_e32 v56, 0xbfb8aa3b, v63
	v_mul_f32_e32 v57, 0xbfb8aa3b, v62
	v_exp_f32_e32 v56, v56
	v_exp_f32_e32 v57, v57
	v_addc_co_u32_e64 v1, s[6:7], 0, v81, s[6:7]
	v_rcp_f32_e32 v54, v54
	s_nop 0
	v_mul_f32_e32 v54, v59, v54
	v_pk_add_f32 v[56:57], v[56:57], 1.0 op_sel_hi:[1,0]
	v_and_b32_e32 v58, 0xffff0000, v5
	global_load_dwordx4 v[0:3], v[0:1], off offset:512
	v_and_b32_e32 v64, 0xffff0000, v4
	v_mul_f32_e32 v4, 0xbfb8aa3b, v64
	v_rcp_f32_e32 v57, v57
	s_nop 0
	v_mul_f32_e32 v57, v62, v57
	v_exp_f32_e32 v4, v4
	v_mul_f32_e32 v5, 0xbfb8aa3b, v58
	v_exp_f32_e32 v5, v5
	s_nop 0
	v_pk_add_f32 v[4:5], v[4:5], 1.0 op_sel_hi:[1,0]
	v_rcp_f32_e32 v56, v56
	s_nop 0
	v_mul_f32_e32 v56, v63, v56
	v_lshlrev_b32_e32 v65, 16, v6
	v_rcp_f32_e32 v59, v5
	s_nop 0
	v_mul_f32_e32 v59, v58, v59
	v_lshlrev_b32_e32 v62, 16, v7
	v_mul_f32_e32 v60, 0xbfb8aa3b, v65
	v_mul_f32_e32 v61, 0xbfb8aa3b, v62
	v_exp_f32_e32 v60, v60
	v_exp_f32_e32 v61, v61
	v_rcp_f32_e32 v58, v4
	s_nop 0
	v_mul_f32_e32 v58, v64, v58
	v_and_b32_e32 v63, 0xffff0000, v7
	v_pk_add_f32 v[4:5], v[60:61], 1.0 op_sel_hi:[1,0]
	v_and_b32_e32 v64, 0xffff0000, v6
	v_mul_f32_e32 v6, 0xbfb8aa3b, v64
	v_exp_f32_e32 v6, v6
	v_rcp_f32_e32 v61, v5
	s_nop 0
	v_mul_f32_e32 v61, v62, v61
	v_mul_f32_e32 v7, 0xbfb8aa3b, v63
	v_exp_f32_e32 v7, v7
	s_nop 0
	v_pk_add_f32 v[6:7], v[6:7], 1.0 op_sel_hi:[1,0]
	v_rcp_f32_e32 v60, v4
	s_nop 0
	v_mul_f32_e32 v60, v65, v60
	v_rcp_f32_e32 v4, v7
	s_nop 0
	v_mul_f32_e32 v63, v63, v4
	s_waitcnt vmcnt(0)
	v_lshlrev_b32_e32 v66, 16, v1
	v_lshlrev_b32_e32 v67, 16, v0
	v_mul_f32_e32 v4, 0xbfb8aa3b, v67
	v_mul_f32_e32 v5, 0xbfb8aa3b, v66
	v_exp_f32_e32 v4, v4
	v_exp_f32_e32 v5, v5
	v_and_b32_e32 v68, 0xffff0000, v1
	v_rcp_f32_e32 v62, v6
	s_nop 0
	v_mul_f32_e32 v62, v64, v62
	v_pk_add_f32 v[4:5], v[4:5], 1.0 op_sel_hi:[1,0]
	v_and_b32_e32 v69, 0xffff0000, v0
	v_mul_f32_e32 v0, 0xbfb8aa3b, v69
	v_exp_f32_e32 v6, v0
	v_and_b32_e32 v80, 0xffff0000, v2
	v_rcp_f32_e32 v1, v5
	s_nop 0
	v_mul_f32_e32 v1, v66, v1
	v_mul_f32_e32 v7, 0xbfb8aa3b, v68
	v_exp_f32_e32 v7, v7
	s_nop 0
	v_pk_add_f32 v[64:65], v[6:7], 1.0 op_sel_hi:[1,0]
	v_rcp_f32_e32 v0, v4
	s_nop 0
	v_mul_f32_e32 v0, v67, v0
	v_rcp_f32_e32 v65, v65
	s_nop 0
	v_mul_f32_e32 v65, v68, v65
	v_add_co_u32_e64 v4, s[6:7], s73, v78
	s_nop 0
	s_nop 0
	v_addc_co_u32_e64 v5, s[6:7], 0, v79, s[6:7]
	global_load_dwordx4 v[4:7], v[4:5], off offset:512
	v_lshlrev_b32_e32 v78, 16, v3
	v_lshlrev_b32_e32 v79, 16, v2
	v_mul_f32_e32 v66, 0xbfb8aa3b, v79
	v_mul_f32_e32 v67, 0xbfb8aa3b, v78
	v_exp_f32_e32 v66, v66
	v_exp_f32_e32 v67, v67
	v_and_b32_e32 v70, 0xffff0000, v3
	v_rcp_f32_e32 v64, v64
	s_nop 0
	v_mul_f32_e32 v64, v69, v64
	v_pk_add_f32 v[66:67], v[66:67], 1.0 op_sel_hi:[1,0]
	v_mul_f32_e32 v2, 0xbfb8aa3b, v80
	v_exp_f32_e32 v68, v2
	v_mul_f32_e32 v69, 0xbfb8aa3b, v70
	v_exp_f32_e32 v69, v69
	v_rcp_f32_e32 v3, v67
	s_nop 0
	v_mul_f32_e32 v3, v78, v3
	v_pk_add_f32 v[68:69], v[68:69], 1.0 op_sel_hi:[1,0]
	v_rcp_f32_e32 v2, v66
	s_nop 0
	v_mul_f32_e32 v2, v79, v2
	v_rcp_f32_e32 v67, v69
	s_nop 0
	v_mul_f32_e32 v67, v70, v67
	v_add_co_u32_e64 v70, s[6:7], s73, v76
	s_nop 0
	s_nop 0
	v_addc_co_u32_e64 v71, s[6:7], 0, v77, s[6:7]
	global_load_dwordx4 v[76:79], v[70:71], off offset:512
	v_rcp_f32_e32 v66, v68
	s_nop 0
	v_mul_f32_e32 v66, v80, v66
	s_waitcnt vmcnt(1)
	v_lshlrev_b32_e32 v82, 16, v5
	v_lshlrev_b32_e32 v83, 16, v4
	v_mul_f32_e32 v70, 0xbfb8aa3b, v83
	v_mul_f32_e32 v71, 0xbfb8aa3b, v82
	v_exp_f32_e32 v70, v70
	v_exp_f32_e32 v71, v71
	v_and_b32_e32 v80, 0xffff0000, v5
	v_and_b32_e32 v84, 0xffff0000, v4
	v_mul_f32_e32 v4, 0xbfb8aa3b, v84
	v_pk_add_f32 v[68:69], v[70:71], 1.0 op_sel_hi:[1,0]
	v_exp_f32_e32 v70, v4
	s_waitcnt lgkmcnt(0)
	s_barrier
; __device__ __forceinline__ unsigned pack2(float a, float b) { return (unsigned)f2bf(a) | ((unsigned)f2bf(b) << 16); }
; __device__ __forceinline__ float bflo(unsigned w) { return __uint_as_float(w << 16); }
; __device__ __forceinline__ float bfhi(unsigned w) { return __uint_as_float(w & 0xffff0000u); }
; __device__ __forceinline__ float silu_f(float g) { return g / (1.f + __expf(-g)); }
; template <int DH, int MODE>
; __device__ void attn_item(const Params& p, int layer, int b, int blk, int head, char* smem) {
;     ...
;     for (int i = 0; i < NCH; ++i) {
;       int q = tid + 256 * i, r = q / CPR, c = (q % CPR) * 8;
;       float4 m0 = *reinterpret_cast<const float4*>(Of + r * OST + c);
;       float4 m1 = *reinterpret_cast<const float4*>(Of + r * OST + c + 4);
;       float mm[8] = {m0.x, m0.y, m0.z, m0.w, m1.x, m1.y, m1.z, m1.w};
;       unsigned gw[4] = {gt[i].x, gt[i].y, gt[i].z, gt[i].w};
;       unsigned ow[4];
; #pragma unroll
;       for (int e = 0; e < 4; ++e)
;         ow[e] = pack2(mm[2 * e] * silu_f(bflo(gw[e])), mm[2 * e + 1] * silu_f(bfhi(gw[e])));
;       *reinterpret_cast<uint4*>(Y + (tq0 + r) * YW + ycol + c) = make_uint4(ow[0], ow[1], ow[2], ow[3]);
;     }
	v_mul_f32_e32 v71, 0xbfb8aa3b, v80
	v_exp_f32_e32 v71, v71
	v_rcp_f32_e32 v5, v69
	s_nop 0
	v_mul_f32_e32 v5, v82, v5
	v_pk_add_f32 v[70:71], v[70:71], 1.0 op_sel_hi:[1,0]
	v_rcp_f32_e32 v4, v68
	s_nop 0
	v_mul_f32_e32 v4, v83, v4
	v_rcp_f32_e32 v69, v71
	s_nop 0
	v_mul_f32_e32 v69, v80, v69
	v_lshlrev_b32_e32 v82, 16, v7
	v_lshlrev_b32_e32 v85, 16, v6
	v_mul_f32_e32 v80, 0xbfb8aa3b, v85
	v_mul_f32_e32 v81, 0xbfb8aa3b, v82
	v_exp_f32_e32 v80, v80
	v_exp_f32_e32 v81, v81
	v_rcp_f32_e32 v68, v70
	s_nop 0
	v_mul_f32_e32 v68, v84, v68
	v_and_b32_e32 v83, 0xffff0000, v7
	v_pk_add_f32 v[70:71], v[80:81], 1.0 op_sel_hi:[1,0]
	v_and_b32_e32 v84, 0xffff0000, v6
	v_mul_f32_e32 v6, 0xbfb8aa3b, v84
	v_exp_f32_e32 v80, v6
	s_waitcnt vmcnt(0)
	v_and_b32_e32 v94, 0xffff0000, v78
	v_mul_f32_e32 v81, 0xbfb8aa3b, v83
	v_exp_f32_e32 v81, v81
	v_rcp_f32_e32 v7, v71
	s_nop 0
	v_mul_f32_e32 v7, v82, v7
	v_pk_add_f32 v[80:81], v[80:81], 1.0 op_sel_hi:[1,0]
	v_rcp_f32_e32 v6, v70
	s_nop 0
	v_mul_f32_e32 v6, v85, v6
	v_rcp_f32_e32 v71, v81
	s_nop 0
	v_mul_f32_e32 v71, v83, v71
	v_lshlrev_b32_e32 v86, 16, v77
	v_lshlrev_b32_e32 v87, 16, v76
	v_mul_f32_e32 v82, 0xbfb8aa3b, v87
	v_mul_f32_e32 v83, 0xbfb8aa3b, v86
	v_exp_f32_e32 v82, v82
	v_exp_f32_e32 v83, v83
	v_rcp_f32_e32 v70, v80
	s_nop 0
	v_mul_f32_e32 v70, v84, v70
	v_and_b32_e32 v88, 0xffff0000, v77
	v_pk_add_f32 v[80:81], v[82:83], 1.0 op_sel_hi:[1,0]
	v_and_b32_e32 v83, 0xffff0000, v76
	v_mul_f32_e32 v76, 0xbfb8aa3b, v83
	v_exp_f32_e32 v76, v76
	v_rcp_f32_e32 v85, v81
	s_nop 0
	v_mul_f32_e32 v85, v86, v85
	v_mul_f32_e32 v77, 0xbfb8aa3b, v88
	v_exp_f32_e32 v77, v77
	s_nop 0
	v_pk_add_f32 v[76:77], v[76:77], 1.0 op_sel_hi:[1,0]
	v_rcp_f32_e32 v84, v80
	s_nop 0
	v_mul_f32_e32 v84, v87, v84
	v_rcp_f32_e32 v87, v77
	s_nop 0
	v_mul_f32_e32 v87, v88, v87
	v_lshlrev_b32_e32 v90, 16, v78
	v_lshlrev_b32_e32 v82, 16, v79
	v_mul_f32_e32 v80, 0xbfb8aa3b, v90
	v_mul_f32_e32 v81, 0xbfb8aa3b, v82
	v_exp_f32_e32 v80, v80
	v_exp_f32_e32 v81, v81
	v_rcp_f32_e32 v86, v76
	s_nop 0
	v_mul_f32_e32 v86, v83, v86
	v_and_b32_e32 v83, 0xffff0000, v79
	v_pk_add_f32 v[76:77], v[80:81], 1.0 op_sel_hi:[1,0]
	v_mul_f32_e32 v78, 0xbfb8aa3b, v94
	v_exp_f32_e32 v78, v78
	v_rcp_f32_e32 v89, v77
	s_nop 0
	v_mul_f32_e32 v89, v82, v89
	v_mul_f32_e32 v79, 0xbfb8aa3b, v83
	v_exp_f32_e32 v79, v79
	s_nop 0
	v_pk_add_f32 v[80:81], v[78:79], 1.0 op_sel_hi:[1,0]
	v_rcp_f32_e32 v88, v76
	s_nop 0
	v_mul_f32_e32 v88, v90, v88
	v_rcp_f32_e32 v91, v81
	s_nop 0
	v_mul_f32_e32 v91, v83, v91
	ds_read_b128 v[76:79], v98
	v_rcp_f32_e32 v90, v80
	s_nop 0
	v_mul_f32_e32 v90, v94, v90
	ds_read_b128 v[80:83], v98 offset:16
	v_add_co_u32_e32 v30, vcc, s70, v30
	s_waitcnt lgkmcnt(1)
	v_mov_b32_e32 v96, v76
	v_mov_b32_e32 v97, v78
	v_pk_mul_f32 v[84:85], v[84:85], v[96:97]
	v_mov_b32_e32 v78, v77
	v_pk_mul_f32 v[76:77], v[86:87], v[78:79]
	v_cvt_pk_bf16_f32 v79, 0, v84
	v_cvt_pk_bf16_f32 v78, 0, v85
	v_cvt_pk_bf16_f32 v77, 0, v77
	v_cvt_pk_bf16_f32 v76, 0, v76
	v_and_b32_e32 v77, 0xffff0000, v77
	v_and_b32_e32 v76, 0xffff0000, v76
	v_or_b32_sdwa v77, v77, v78 dst_sel:DWORD dst_unused:UNUSED_PAD src0_sel:DWORD src1_sel:WORD_1
	v_or_b32_sdwa v76, v76, v79 dst_sel:DWORD dst_unused:UNUSED_PAD src0_sel:DWORD src1_sel:WORD_1
	s_waitcnt lgkmcnt(0)
	v_mov_b32_e32 v78, v80
	v_mov_b32_e32 v79, v82
	v_pk_mul_f32 v[78:79], v[88:89], v[78:79]
	v_mov_b32_e32 v82, v81
	v_pk_mul_f32 v[80:81], v[90:91], v[82:83]
	v_cvt_pk_bf16_f32 v78, 0, v78
	v_cvt_pk_bf16_f32 v79, 0, v79
	v_cvt_pk_bf16_f32 v81, 0, v81
	v_cvt_pk_bf16_f32 v80, 0, v80
	v_and_b32_e32 v81, 0xffff0000, v81
	v_and_b32_e32 v80, 0xffff0000, v80
	v_or_b32_sdwa v79, v81, v79 dst_sel:DWORD dst_unused:UNUSED_PAD src0_sel:DWORD src1_sel:WORD_1
	v_or_b32_sdwa v78, v80, v78 dst_sel:DWORD dst_unused:UNUSED_PAD src0_sel:DWORD src1_sel:WORD_1
	ds_read_b128 v[80:83], v95
	v_addc_co_u32_e32 v31, vcc, 0, v31, vcc
	global_store_dwordx4 v[30:31], v[76:79], off offset:2048
	s_nop 0
	ds_read_b128 v[76:79], v95 offset:16
	s_waitcnt lgkmcnt(1)
	v_mov_b32_e32 v30, v80
	v_mov_b32_e32 v31, v82
	v_pk_mul_f32 v[4:5], v[4:5], v[30:31]
	v_mov_b32_e32 v82, v81
	v_pk_mul_f32 v[30:31], v[68:69], v[82:83]
	v_cvt_pk_bf16_f32 v4, 0, v4
	v_cvt_pk_bf16_f32 v5, 0, v5
	v_cvt_pk_bf16_f32 v31, 0, v31
	v_cvt_pk_bf16_f32 v30, 0, v30
	v_and_b32_e32 v31, 0xffff0000, v31
	v_and_b32_e32 v30, 0xffff0000, v30
	v_or_b32_sdwa v5, v31, v5 dst_sel:DWORD dst_unused:UNUSED_PAD src0_sel:DWORD src1_sel:WORD_1
	v_or_b32_sdwa v4, v30, v4 dst_sel:DWORD dst_unused:UNUSED_PAD src0_sel:DWORD src1_sel:WORD_1
	s_waitcnt lgkmcnt(0)
	v_mov_b32_e32 v30, v76
	v_mov_b32_e32 v31, v78
	v_pk_mul_f32 v[6:7], v[6:7], v[30:31]
	v_mov_b32_e32 v78, v77
	v_pk_mul_f32 v[30:31], v[70:71], v[78:79]
	v_cvt_pk_bf16_f32 v6, 0, v6
	v_cvt_pk_bf16_f32 v7, 0, v7
	v_cvt_pk_bf16_f32 v31, 0, v31
	v_cvt_pk_bf16_f32 v30, 0, v30
	ds_read_b128 v[68:71], v93
	v_and_b32_e32 v31, 0xffff0000, v31
	v_and_b32_e32 v30, 0xffff0000, v30
	v_add_co_u32_e32 v26, vcc, s70, v26
	v_or_b32_sdwa v7, v31, v7 dst_sel:DWORD dst_unused:UNUSED_PAD src0_sel:DWORD src1_sel:WORD_1
	v_or_b32_sdwa v6, v30, v6 dst_sel:DWORD dst_unused:UNUSED_PAD src0_sel:DWORD src1_sel:WORD_1
	v_addc_co_u32_e32 v27, vcc, 0, v27, vcc
	global_store_dwordx4 v[26:27], v[4:7], off offset:2048
	s_waitcnt lgkmcnt(0)
	v_mov_b32_e32 v26, v68
	v_mov_b32_e32 v27, v70
	ds_read_b128 v[4:7], v93 offset:16
	v_pk_mul_f32 v[0:1], v[0:1], v[26:27]
	v_mov_b32_e32 v70, v69
	v_pk_mul_f32 v[26:27], v[64:65], v[70:71]
	v_cvt_pk_bf16_f32 v0, 0, v0
	v_cvt_pk_bf16_f32 v1, 0, v1
	v_cvt_pk_bf16_f32 v27, 0, v27
	v_cvt_pk_bf16_f32 v26, 0, v26
	v_and_b32_e32 v27, 0xffff0000, v27
	v_and_b32_e32 v26, 0xffff0000, v26
	v_or_b32_sdwa v1, v27, v1 dst_sel:DWORD dst_unused:UNUSED_PAD src0_sel:DWORD src1_sel:WORD_1
	v_or_b32_sdwa v0, v26, v0 dst_sel:DWORD dst_unused:UNUSED_PAD src0_sel:DWORD src1_sel:WORD_1
	s_waitcnt lgkmcnt(0)
; __device__ __forceinline__ unsigned pack2(float a, float b) { return (unsigned)f2bf(a) | ((unsigned)f2bf(b) << 16); }
; __device__ __forceinline__ float bflo(unsigned w) { return __uint_as_float(w << 16); }
; __device__ __forceinline__ float bfhi(unsigned w) { return __uint_as_float(w & 0xffff0000u); }
; __device__ __forceinline__ float silu_f(float g) { return g / (1.f + __expf(-g)); }
; template <int DH, int MODE>
; __device__ void attn_item(const Params& p, int layer, int b, int blk, int head, char* smem) {
;     ...
;     for (int i = 0; i < NCH; ++i) {
;       int q = tid + 256 * i, r = q / CPR, c = (q % CPR) * 8;
;       float4 m0 = *reinterpret_cast<const float4*>(Of + r * OST + c);
;       float4 m1 = *reinterpret_cast<const float4*>(Of + r * OST + c + 4);
;       float mm[8] = {m0.x, m0.y, m0.z, m0.w, m1.x, m1.y, m1.z, m1.w};
;       unsigned gw[4] = {gt[i].x, gt[i].y, gt[i].z, gt[i].w};
;       unsigned ow[4];
; #pragma unroll
;       for (int e = 0; e < 4; ++e)
;         ow[e] = pack2(mm[2 * e] * silu_f(bflo(gw[e])), mm[2 * e + 1] * silu_f(bfhi(gw[e])));
;       *reinterpret_cast<uint4*>(Y + (tq0 + r) * YW + ycol + c) = make_uint4(ow[0], ow[1], ow[2], ow[3]);
;     }
	v_mov_b32_e32 v26, v4
	v_mov_b32_e32 v27, v6
	v_pk_mul_f32 v[2:3], v[2:3], v[26:27]
	v_mov_b32_e32 v6, v5
	v_pk_mul_f32 v[4:5], v[66:67], v[6:7]
	v_cvt_pk_bf16_f32 v2, 0, v2
	v_cvt_pk_bf16_f32 v3, 0, v3
	v_cvt_pk_bf16_f32 v5, 0, v5
	v_cvt_pk_bf16_f32 v4, 0, v4
	v_and_b32_e32 v5, 0xffff0000, v5
	v_and_b32_e32 v4, 0xffff0000, v4
	v_or_b32_sdwa v3, v5, v3 dst_sel:DWORD dst_unused:UNUSED_PAD src0_sel:DWORD src1_sel:WORD_1
	v_or_b32_sdwa v2, v4, v2 dst_sel:DWORD dst_unused:UNUSED_PAD src0_sel:DWORD src1_sel:WORD_1
	ds_read_b128 v[4:7], v92
	v_add_co_u32_e32 v20, vcc, s70, v20
	s_nop 1
	v_addc_co_u32_e32 v21, vcc, 0, v21, vcc
	global_store_dwordx4 v[20:21], v[0:3], off offset:2048
	s_waitcnt lgkmcnt(0)
	v_mov_b32_e32 v20, v4
	v_mov_b32_e32 v21, v6
	ds_read_b128 v[0:3], v92 offset:16
	v_pk_mul_f32 v[20:21], v[56:57], v[20:21]
	v_mov_b32_e32 v6, v5
	v_pk_mul_f32 v[4:5], v[58:59], v[6:7]
	v_cvt_pk_bf16_f32 v7, 0, v20
	v_cvt_pk_bf16_f32 v6, 0, v21
	v_cvt_pk_bf16_f32 v5, 0, v5
	v_cvt_pk_bf16_f32 v4, 0, v4
	v_and_b32_e32 v5, 0xffff0000, v5
	v_and_b32_e32 v4, 0xffff0000, v4
	v_or_b32_sdwa v5, v5, v6 dst_sel:DWORD dst_unused:UNUSED_PAD src0_sel:DWORD src1_sel:WORD_1
	v_or_b32_sdwa v4, v4, v7 dst_sel:DWORD dst_unused:UNUSED_PAD src0_sel:DWORD src1_sel:WORD_1
	s_waitcnt lgkmcnt(0)
	v_mov_b32_e32 v6, v0
	v_mov_b32_e32 v7, v2
	v_pk_mul_f32 v[6:7], v[60:61], v[6:7]
	v_mov_b32_e32 v2, v1
	v_pk_mul_f32 v[0:1], v[62:63], v[2:3]
	v_cvt_pk_bf16_f32 v3, 0, v6
	v_cvt_pk_bf16_f32 v2, 0, v7
	v_cvt_pk_bf16_f32 v1, 0, v1
	v_cvt_pk_bf16_f32 v0, 0, v0
	v_and_b32_e32 v1, 0xffff0000, v1
	v_and_b32_e32 v0, 0xffff0000, v0
	v_or_b32_sdwa v7, v1, v2 dst_sel:DWORD dst_unused:UNUSED_PAD src0_sel:DWORD src1_sel:WORD_1
	v_or_b32_sdwa v6, v0, v3 dst_sel:DWORD dst_unused:UNUSED_PAD src0_sel:DWORD src1_sel:WORD_1
	ds_read_b128 v[0:3], v75
	v_add_co_u32_e32 v16, vcc, s70, v16
	s_nop 1
	v_addc_co_u32_e32 v17, vcc, 0, v17, vcc
	global_store_dwordx4 v[16:17], v[4:7], off offset:2048
	s_waitcnt lgkmcnt(0)
	v_mov_b32_e32 v16, v0
	v_mov_b32_e32 v17, v2
	ds_read_b128 v[4:7], v75 offset:16
	v_pk_mul_f32 v[16:17], v[48:49], v[16:17]
	v_mov_b32_e32 v2, v1
	v_pk_mul_f32 v[0:1], v[50:51], v[2:3]
	v_cvt_pk_bf16_f32 v3, 0, v16
	v_cvt_pk_bf16_f32 v2, 0, v17
	v_cvt_pk_bf16_f32 v1, 0, v1
	v_cvt_pk_bf16_f32 v0, 0, v0
	v_and_b32_e32 v1, 0xffff0000, v1
	v_and_b32_e32 v0, 0xffff0000, v0
	v_or_b32_sdwa v1, v1, v2 dst_sel:DWORD dst_unused:UNUSED_PAD src0_sel:DWORD src1_sel:WORD_1
	v_or_b32_sdwa v0, v0, v3 dst_sel:DWORD dst_unused:UNUSED_PAD src0_sel:DWORD src1_sel:WORD_1
	s_waitcnt lgkmcnt(0)
	v_mov_b32_e32 v2, v4
	v_mov_b32_e32 v3, v6
	v_pk_mul_f32 v[2:3], v[52:53], v[2:3]
	v_mov_b32_e32 v6, v5
	v_pk_mul_f32 v[4:5], v[54:55], v[6:7]
	v_cvt_pk_bf16_f32 v2, 0, v2
	v_cvt_pk_bf16_f32 v3, 0, v3
	v_cvt_pk_bf16_f32 v5, 0, v5
	v_cvt_pk_bf16_f32 v4, 0, v4
	v_and_b32_e32 v5, 0xffff0000, v5
	v_and_b32_e32 v4, 0xffff0000, v4
	v_or_b32_sdwa v3, v5, v3 dst_sel:DWORD dst_unused:UNUSED_PAD src0_sel:DWORD src1_sel:WORD_1
	v_or_b32_sdwa v2, v4, v2 dst_sel:DWORD dst_unused:UNUSED_PAD src0_sel:DWORD src1_sel:WORD_1
	ds_read_b128 v[4:7], v74
	v_add_co_u32_e32 v12, vcc, s70, v12
	s_nop 1
	v_addc_co_u32_e32 v13, vcc, 0, v13, vcc
	global_store_dwordx4 v[12:13], v[0:3], off offset:2048
	s_waitcnt lgkmcnt(0)
; __device__ __forceinline__ unsigned pack2(float a, float b) { return (unsigned)f2bf(a) | ((unsigned)f2bf(b) << 16); }
; __device__ __forceinline__ float bflo(unsigned w) { return __uint_as_float(w << 16); }
; __device__ __forceinline__ float bfhi(unsigned w) { return __uint_as_float(w & 0xffff0000u); }
; __device__ __forceinline__ float silu_f(float g) { return g / (1.f + __expf(-g)); }
; template <int DH, int MODE>
; __device__ void attn_item(const Params& p, int layer, int b, int blk, int head, char* smem) {
;     ...
;     for (int i = 0; i < NCH; ++i) {
;       int q = tid + 256 * i, r = q / CPR, c = (q % CPR) * 8;
;       float4 m0 = *reinterpret_cast<const float4*>(Of + r * OST + c);
;       float4 m1 = *reinterpret_cast<const float4*>(Of + r * OST + c + 4);
;       float mm[8] = {m0.x, m0.y, m0.z, m0.w, m1.x, m1.y, m1.z, m1.w};
;       unsigned gw[4] = {gt[i].x, gt[i].y, gt[i].z, gt[i].w};
;       unsigned ow[4];
; #pragma unroll
;       for (int e = 0; e < 4; ++e)
;         ow[e] = pack2(mm[2 * e] * silu_f(bflo(gw[e])), mm[2 * e + 1] * silu_f(bfhi(gw[e])));
;       *reinterpret_cast<uint4*>(Y + (tq0 + r) * YW + ycol + c) = make_uint4(ow[0], ow[1], ow[2], ow[3]);
;     }
	v_mov_b32_e32 v12, v4
	v_mov_b32_e32 v13, v6
	ds_read_b128 v[0:3], v74 offset:16
	v_pk_mul_f32 v[12:13], v[40:41], v[12:13]
	v_mov_b32_e32 v6, v5
	v_pk_mul_f32 v[4:5], v[42:43], v[6:7]
	v_cvt_pk_bf16_f32 v7, 0, v12
	v_cvt_pk_bf16_f32 v6, 0, v13
	v_cvt_pk_bf16_f32 v5, 0, v5
	v_cvt_pk_bf16_f32 v4, 0, v4
	v_and_b32_e32 v5, 0xffff0000, v5
	v_and_b32_e32 v4, 0xffff0000, v4
	v_or_b32_sdwa v5, v5, v6 dst_sel:DWORD dst_unused:UNUSED_PAD src0_sel:DWORD src1_sel:WORD_1
	v_or_b32_sdwa v4, v4, v7 dst_sel:DWORD dst_unused:UNUSED_PAD src0_sel:DWORD src1_sel:WORD_1
	s_waitcnt lgkmcnt(0)
	v_mov_b32_e32 v6, v0
	v_mov_b32_e32 v7, v2
	v_pk_mul_f32 v[6:7], v[44:45], v[6:7]
	v_mov_b32_e32 v2, v1
	v_pk_mul_f32 v[0:1], v[46:47], v[2:3]
	v_cvt_pk_bf16_f32 v3, 0, v6
	v_cvt_pk_bf16_f32 v2, 0, v7
	v_cvt_pk_bf16_f32 v1, 0, v1
	v_cvt_pk_bf16_f32 v0, 0, v0
	v_and_b32_e32 v1, 0xffff0000, v1
	v_and_b32_e32 v0, 0xffff0000, v0
	v_or_b32_sdwa v7, v1, v2 dst_sel:DWORD dst_unused:UNUSED_PAD src0_sel:DWORD src1_sel:WORD_1
	v_or_b32_sdwa v6, v0, v3 dst_sel:DWORD dst_unused:UNUSED_PAD src0_sel:DWORD src1_sel:WORD_1
	ds_read_b128 v[0:3], v73
	v_add_co_u32_e32 v10, vcc, s70, v10
	s_nop 1
	v_addc_co_u32_e32 v11, vcc, 0, v11, vcc
	global_store_dwordx4 v[10:11], v[4:7], off offset:2048
	s_waitcnt lgkmcnt(0)
	v_mov_b32_e32 v10, v0
	v_mov_b32_e32 v11, v2
	ds_read_b128 v[4:7], v73 offset:16
	v_pk_mul_f32 v[10:11], v[32:33], v[10:11]
	v_mov_b32_e32 v2, v1
	v_pk_mul_f32 v[0:1], v[34:35], v[2:3]
	v_cvt_pk_bf16_f32 v3, 0, v10
	v_cvt_pk_bf16_f32 v2, 0, v11
	v_cvt_pk_bf16_f32 v1, 0, v1
	v_cvt_pk_bf16_f32 v0, 0, v0
	v_and_b32_e32 v1, 0xffff0000, v1
	v_and_b32_e32 v0, 0xffff0000, v0
	v_or_b32_sdwa v1, v1, v2 dst_sel:DWORD dst_unused:UNUSED_PAD src0_sel:DWORD src1_sel:WORD_1
	v_or_b32_sdwa v0, v0, v3 dst_sel:DWORD dst_unused:UNUSED_PAD src0_sel:DWORD src1_sel:WORD_1
	s_waitcnt lgkmcnt(0)
	v_mov_b32_e32 v2, v4
	v_mov_b32_e32 v3, v6
	v_pk_mul_f32 v[2:3], v[36:37], v[2:3]
	v_mov_b32_e32 v6, v5
	v_pk_mul_f32 v[4:5], v[38:39], v[6:7]
	v_cvt_pk_bf16_f32 v2, 0, v2
	v_cvt_pk_bf16_f32 v3, 0, v3
	v_cvt_pk_bf16_f32 v5, 0, v5
	v_cvt_pk_bf16_f32 v4, 0, v4
	v_and_b32_e32 v5, 0xffff0000, v5
	v_and_b32_e32 v4, 0xffff0000, v4
	v_or_b32_sdwa v3, v5, v3 dst_sel:DWORD dst_unused:UNUSED_PAD src0_sel:DWORD src1_sel:WORD_1
	v_or_b32_sdwa v2, v4, v2 dst_sel:DWORD dst_unused:UNUSED_PAD src0_sel:DWORD src1_sel:WORD_1
	ds_read_b128 v[4:7], v72
	v_add_co_u32_e32 v8, vcc, s70, v8
	s_nop 1
	v_addc_co_u32_e32 v9, vcc, 0, v9, vcc
	global_store_dwordx4 v[8:9], v[0:3], off offset:2048
	s_waitcnt lgkmcnt(0)
	v_mov_b32_e32 v8, v4
	v_mov_b32_e32 v9, v6
	ds_read_b128 v[0:3], v72 offset:16
	v_pk_mul_f32 v[8:9], v[18:19], v[8:9]
	v_mov_b32_e32 v6, v5
	v_pk_mul_f32 v[4:5], v[22:23], v[6:7]
	v_cvt_pk_bf16_f32 v7, 0, v8
	v_cvt_pk_bf16_f32 v6, 0, v9
	v_cvt_pk_bf16_f32 v5, 0, v5
	v_cvt_pk_bf16_f32 v4, 0, v4
	v_and_b32_e32 v5, 0xffff0000, v5
	v_and_b32_e32 v4, 0xffff0000, v4
	v_or_b32_sdwa v5, v5, v6 dst_sel:DWORD dst_unused:UNUSED_PAD src0_sel:DWORD src1_sel:WORD_1
	v_or_b32_sdwa v4, v4, v7 dst_sel:DWORD dst_unused:UNUSED_PAD src0_sel:DWORD src1_sel:WORD_1
	s_waitcnt lgkmcnt(0)
	v_mov_b32_e32 v6, v0
	v_mov_b32_e32 v7, v2
	v_pk_mul_f32 v[6:7], v[24:25], v[6:7]
	v_mov_b32_e32 v2, v1
	v_pk_mul_f32 v[0:1], v[28:29], v[2:3]
	v_cvt_pk_bf16_f32 v2, 0, v7
	v_cvt_pk_bf16_f32 v3, 0, v6
	v_cvt_pk_bf16_f32 v0, 0, v0
	v_cvt_pk_bf16_f32 v1, 0, v1
	v_and_b32_e32 v0, 0xffff0000, v0
	v_and_b32_e32 v1, 0xffff0000, v1
	v_or_b32_sdwa v6, v0, v3 dst_sel:DWORD dst_unused:UNUSED_PAD src0_sel:DWORD src1_sel:WORD_1
	v_add_co_u32_e32 v0, vcc, 0x184a1000, v14
	v_or_b32_sdwa v7, v1, v2 dst_sel:DWORD dst_unused:UNUSED_PAD src0_sel:DWORD src1_sel:WORD_1
	s_nop 0
	v_addc_co_u32_e32 v1, vcc, 0, v15, vcc
	global_store_dwordx4 v[0:1], v[4:7], off offset:2048
	s_barrier

; __device__ __forceinline__ float bflo(unsigned w) { return __uint_as_float(w << 16); }
; __device__ __forceinline__ float bfhi(unsigned w) { return __uint_as_float(w & 0xffff0000u); }
; __device__ void gmlp_item(const Params& p, int layer, int b, int n, int g, char* smem) {
;     ...
;   {
;     uint4 raw[8];
; #pragma unroll
;     for (int i = 0; i < 8; ++i) {
;       int q = tid + 256 * i;
;       int st = q & 127, c0 = (q >> 7) * 8;
;       raw[i] = *reinterpret_cast<const uint4*>(P + (t0 + st) * NP + 512 + g * 128 + c0);
;     }
; #pragma unroll
;     for (int i = 0; i < 8; ++i) {
;       int q = tid + 256 * i;
;       int st = q & 127, c0 = (q >> 7) * 8;
;       unsigned w[4] = {raw[i].x, raw[i].y, raw[i].z, raw[i].w};
;       float mu = mu_s[st], rs = rs_s[st];
;       const float4* gp = reinterpret_cast<const float4*>(p.gm_gain + (size_t)layer * 512 + g * 128 + c0);
;       float4 g0 = gp[0], g1 = gp[1];
;       float gg[8] = {g0.x, g0.y, g0.z, g0.w, g1.x, g1.y, g1.z, g1.w};
; #pragma unroll
;       for (int e = 0; e < 8; ++e) {
;         float v = (e & 1) ? bfhi(w[e >> 1]) : bflo(w[e >> 1]);
;         float val = (v - mu) * rs * gg[e];
;         *reinterpret_cast<u16*>(smem + 32768 + (st >> 5) * 8192 + (c0 + e) * 64 + (st & 31) * 2) = f2bf(val);
;       }
;     }
;   }
.LBB0_1121:
	s_or_b64 exec, exec, s[8:9]
	v_and_b32_e32 v6, 0x7f, v59
	s_ashr_i32 s8, s10, 31
	s_bfe_u32 s12, s75, 0x20003
	s_waitcnt lgkmcnt(0)
	v_or_b32_e32 v0, s16, v6
	s_add_u32 s13, s28, s10
	v_mul_lo_u32 v128, v0, s52
	v_ashrrev_i32_e32 v48, 4, v59
	s_addc_u32 s42, s29, s8
	v_lshl_add_u64 v[0:1], v[128:129], 1, s[6:7]
	s_lshl_b32 s8, s12, 8
	s_mov_b32 s9, s17
	v_and_b32_e32 v2, -8, v48
	v_lshl_add_u64 v[0:1], v[0:1], 0, s[8:9]
	v_ashrrev_i32_e32 v3, 31, v2
	v_lshl_add_u64 v[4:5], v[2:3], 1, v[0:1]
	s_barrier
	global_load_dwordx4 v[28:31], v[4:5], off offset:1024
	s_lshl_b32 s10, s12, 7
	s_lshl_b32 s8, s12, 9
	s_add_u32 s8, s48, s8
	s_addc_u32 s9, s23, 0
	v_lshl_add_u64 v[4:5], v[2:3], 2, s[8:9]
	global_load_dwordx4 v[50:53], v[4:5], off
	global_load_dwordx4 v[70:73], v[4:5], off offset:16
	v_add_u32_e32 v3, 0x100, v59
	v_ashrrev_i32_e32 v68, 4, v3
	v_add_u32_e32 v4, 0x200, v59
	v_lshlrev_b32_e32 v12, 1, v59
	v_and_b32_e32 v54, -8, v68
	v_add_u32_e32 v5, 0x300, v59
	v_lshlrev_b32_e32 v11, 8, v59
	v_ashrrev_i32_e32 v66, 4, v4
	v_and_b32_e32 v4, 62, v12
	v_ashrrev_i32_e32 v55, 31, v54
	v_ashrrev_i32_e32 v64, 4, v5
	v_and_or_b32 v44, v11, s53, v4
	v_lshl_add_u64 v[4:5], v[54:55], 1, v[0:1]
	global_load_dwordx4 v[24:27], v[4:5], off offset:1024
	v_lshl_add_u64 v[4:5], v[54:55], 2, s[8:9]
	global_load_dwordx4 v[74:77], v[4:5], off offset:16
	global_load_dwordx4 v[78:81], v[4:5], off
	v_lshlrev_b32_e32 v3, 2, v6
	v_or_b32_e32 v6, 0x10000, v3
	v_or_b32_e32 v3, 0x10200, v3
	ds_read_b32 v45, v6
	ds_read_b32 v46, v3
	v_add_u32_e32 v7, 0x400, v59
	v_add_u32_e32 v8, 0x500, v59
	v_add_u32_e32 v9, 0x600, v59
	v_add_u32_e32 v10, 0x700, v59
	v_ashrrev_i32_e32 v62, 4, v7
	v_ashrrev_i32_e32 v60, 4, v8
	v_ashrrev_i32_e32 v58, 4, v9
	v_ashrrev_i32_e32 v56, 4, v10
	v_and_b32_e32 v42, -8, v66
	v_and_b32_e32 v40, -8, v64
	v_and_b32_e32 v38, -8, v62
	v_and_b32_e32 v36, -8, v60
	v_and_b32_e32 v34, -8, v58
	v_and_b32_e32 v32, -8, v56
	v_ashrrev_i32_e32 v43, 31, v42
	v_ashrrev_i32_e32 v41, 31, v40
	v_ashrrev_i32_e32 v39, 31, v38
	v_ashrrev_i32_e32 v37, 31, v36
	v_ashrrev_i32_e32 v35, 31, v34
	v_ashrrev_i32_e32 v33, 31, v32
	v_lshl_add_u32 v47, v2, 6, v44
	v_lshl_add_u64 v[2:3], v[42:43], 1, v[0:1]
	v_lshl_add_u64 v[4:5], v[40:41], 1, v[0:1]
	v_lshl_add_u64 v[6:7], v[38:39], 1, v[0:1]
	v_lshl_add_u64 v[8:9], v[36:37], 1, v[0:1]
	v_lshl_add_u64 v[82:83], v[34:35], 1, v[0:1]
	v_lshl_add_u64 v[0:1], v[32:33], 1, v[0:1]
	global_load_dwordx4 v[20:23], v[2:3], off offset:1024
	global_load_dwordx4 v[16:19], v[4:5], off offset:1024
	global_load_dwordx4 v[12:15], v[6:7], off offset:1024
	s_nop 0
	global_load_dwordx4 v[8:11], v[8:9], off offset:1024
	s_nop 0
	global_load_dwordx4 v[4:7], v[82:83], off offset:1024
	s_nop 0
	global_load_dwordx4 v[0:3], v[0:1], off offset:1024
	v_and_b32_e32 v49, 15, v59
	v_lshlrev_b32_e32 v128, 4, v49
	s_waitcnt vmcnt(11)
	v_lshlrev_b32_e32 v55, 16, v28
	v_and_b32_e32 v28, 0xffff0000, v28
	s_waitcnt lgkmcnt(1)
	v_sub_f32_e32 v55, v55, v45
	v_sub_f32_e32 v28, v28, v45
	s_waitcnt lgkmcnt(0)
	v_mul_f32_e32 v55, v46, v55
	v_mul_f32_e32 v28, v46, v28
	s_waitcnt vmcnt(10)
	v_mul_f32_e32 v50, v55, v50
	v_mul_f32_e32 v28, v28, v51
	v_cvt_pk_bf16_f32 v50, 0, v50
	ds_write_b16_d16_hi v47, v50 offset:32768
	v_cvt_pk_bf16_f32 v28, 0, v28
	ds_write_b16_d16_hi v47, v28 offset:32832
	v_lshlrev_b32_e32 v28, 16, v29
	v_sub_f32_e32 v28, v28, v45
	v_mul_f32_e32 v28, v46, v28
	v_mul_f32_e32 v28, v28, v52
	v_cvt_pk_bf16_f32 v28, 0, v28
	ds_write_b16_d16_hi v47, v28 offset:32896
	v_and_b32_e32 v28, 0xffff0000, v29
	v_sub_f32_e32 v28, v28, v45
	v_mul_f32_e32 v28, v46, v28
	v_mul_f32_e32 v28, v28, v53
	v_cvt_pk_bf16_f32 v28, 0, v28
	ds_write_b16_d16_hi v47, v28 offset:32960
	v_lshlrev_b32_e32 v28, 16, v30
	v_sub_f32_e32 v28, v28, v45
	v_mul_f32_e32 v28, v46, v28
	s_waitcnt vmcnt(9)
	v_mul_f32_e32 v28, v28, v70
	v_cvt_pk_bf16_f32 v28, 0, v28
	ds_write_b16_d16_hi v47, v28 offset:33024
	v_and_b32_e32 v28, 0xffff0000, v30
	v_sub_f32_e32 v28, v28, v45
	v_mul_f32_e32 v28, v46, v28
	v_mul_f32_e32 v28, v28, v71
	v_cvt_pk_bf16_f32 v28, 0, v28
	ds_write_b16_d16_hi v47, v28 offset:33088
	v_lshlrev_b32_e32 v28, 16, v31
	v_sub_f32_e32 v30, v28, v45
	v_lshl_add_u64 v[28:29], v[42:43], 2, s[8:9]
	global_load_dwordx4 v[50:53], v[28:29], off offset:16
	global_load_dwordx4 v[82:85], v[28:29], off
	v_mul_f32_e32 v28, v46, v30
	v_mul_f32_e32 v28, v28, v72
	v_cvt_pk_bf16_f32 v28, 0, v28
	ds_write_b16_d16_hi v47, v28 offset:33152
	v_and_b32_e32 v28, 0xffff0000, v31
	v_sub_f32_e32 v28, v28, v45
	v_mul_f32_e32 v28, v46, v28
	v_mul_f32_e32 v28, v28, v73
	v_cvt_pk_bf16_f32 v28, 0, v28
	v_lshl_or_b32 v29, v48, 6, v159
	v_add_u32_e32 v29, v44, v29
	ds_write_b16_d16_hi v29, v28 offset:32768
	s_waitcnt vmcnt(10)
	v_lshlrev_b32_e32 v28, 16, v24
	v_sub_f32_e32 v28, v28, v45
	v_mul_f32_e32 v28, v46, v28
	v_and_b32_e32 v24, 0xffff0000, v24
	s_waitcnt vmcnt(8)
; __device__ __forceinline__ float bflo(unsigned w) { return __uint_as_float(w << 16); }
; __device__ __forceinline__ float bfhi(unsigned w) { return __uint_as_float(w & 0xffff0000u); }
; __device__ void gmlp_item(const Params& p, int layer, int b, int n, int g, char* smem) {
;     ...
; #pragma unroll
;     for (int i = 0; i < 8; ++i) {
;       int q = tid + 256 * i;
;       int st = q & 127, c0 = (q >> 7) * 8;
;       unsigned w[4] = {raw[i].x, raw[i].y, raw[i].z, raw[i].w};
;       float mu = mu_s[st], rs = rs_s[st];
;       const float4* gp = reinterpret_cast<const float4*>(p.gm_gain + (size_t)layer * 512 + g * 128 + c0);
;       float4 g0 = gp[0], g1 = gp[1];
;       float gg[8] = {g0.x, g0.y, g0.z, g0.w, g1.x, g1.y, g1.z, g1.w};
; #pragma unroll
;       for (int e = 0; e < 8; ++e) {
;         float v = (e & 1) ? bfhi(w[e >> 1]) : bflo(w[e >> 1]);
;         float val = (v - mu) * rs * gg[e];
;         *reinterpret_cast<u16*>(smem + 32768 + (st >> 5) * 8192 + (c0 + e) * 64 + (st & 31) * 2) = f2bf(val);
;       }
;     }
	v_mul_f32_e32 v28, v28, v78
	v_sub_f32_e32 v24, v24, v45
	v_mul_f32_e32 v24, v46, v24
	v_cvt_pk_bf16_f32 v28, 0, v28
	v_lshl_add_u32 v43, v54, 6, v44
	v_mul_f32_e32 v24, v24, v79
	ds_write_b16_d16_hi v43, v28 offset:32768
	v_cvt_pk_bf16_f32 v24, 0, v24
	ds_write_b16_d16_hi v43, v24 offset:32832
	v_lshlrev_b32_e32 v24, 16, v25
	v_sub_f32_e32 v24, v24, v45
	v_mul_f32_e32 v24, v46, v24
	v_mul_f32_e32 v24, v24, v80
	v_cvt_pk_bf16_f32 v24, 0, v24
	ds_write_b16_d16_hi v43, v24 offset:32896
	v_and_b32_e32 v24, 0xffff0000, v25
	v_sub_f32_e32 v24, v24, v45
	v_mul_f32_e32 v24, v46, v24
	v_mul_f32_e32 v24, v24, v81
	v_cvt_pk_bf16_f32 v24, 0, v24
	ds_write_b16_d16_hi v43, v24 offset:32960
	v_lshlrev_b32_e32 v24, 16, v26
	v_sub_f32_e32 v24, v24, v45
	v_mul_f32_e32 v24, v46, v24
	v_mul_f32_e32 v24, v24, v74
	v_cvt_pk_bf16_f32 v24, 0, v24
	ds_write_b16_d16_hi v43, v24 offset:33024
	v_and_b32_e32 v24, 0xffff0000, v26
	v_sub_f32_e32 v24, v24, v45
	v_mul_f32_e32 v24, v46, v24
	v_mul_f32_e32 v24, v24, v75
	v_cvt_pk_bf16_f32 v24, 0, v24
	ds_write_b16_d16_hi v43, v24 offset:33088
	v_lshlrev_b32_e32 v24, 16, v27
	v_sub_f32_e32 v26, v24, v45
	v_lshl_add_u64 v[24:25], v[40:41], 2, s[8:9]
	global_load_dwordx4 v[28:31], v[24:25], off offset:16
	global_load_dwordx4 v[70:73], v[24:25], off
	v_mul_f32_e32 v24, v46, v26
	v_mul_f32_e32 v24, v24, v76
	v_cvt_pk_bf16_f32 v24, 0, v24
	ds_write_b16_d16_hi v43, v24 offset:33152
	v_and_b32_e32 v24, 0xffff0000, v27
	v_sub_f32_e32 v24, v24, v45
	v_mul_f32_e32 v24, v46, v24
	v_mul_f32_e32 v24, v24, v77
	v_cvt_pk_bf16_f32 v24, 0, v24
	v_lshl_or_b32 v25, v68, 6, v159
	v_add_u32_e32 v25, v44, v25
	ds_write_b16_d16_hi v25, v24 offset:32768
	s_waitcnt vmcnt(9)
	v_lshlrev_b32_e32 v24, 16, v20
	v_sub_f32_e32 v24, v24, v45
	v_mul_f32_e32 v24, v46, v24
	v_and_b32_e32 v20, 0xffff0000, v20
	s_waitcnt vmcnt(2)
	v_mul_f32_e32 v24, v24, v82
	v_sub_f32_e32 v20, v20, v45
	v_mul_f32_e32 v20, v46, v20
	v_cvt_pk_bf16_f32 v24, 0, v24
	v_lshl_add_u32 v41, v42, 6, v44
	v_mul_f32_e32 v20, v20, v83
	ds_write_b16_d16_hi v41, v24 offset:32768
	v_cvt_pk_bf16_f32 v20, 0, v20
	ds_write_b16_d16_hi v41, v20 offset:32832
	v_lshlrev_b32_e32 v20, 16, v21
	v_sub_f32_e32 v20, v20, v45
	v_mul_f32_e32 v20, v46, v20
	v_mul_f32_e32 v20, v20, v84
	v_cvt_pk_bf16_f32 v20, 0, v20
	ds_write_b16_d16_hi v41, v20 offset:32896
	v_and_b32_e32 v20, 0xffff0000, v21
	v_sub_f32_e32 v20, v20, v45
	v_mul_f32_e32 v20, v46, v20
	v_mul_f32_e32 v20, v20, v85
	v_cvt_pk_bf16_f32 v20, 0, v20
	ds_write_b16_d16_hi v41, v20 offset:32960
	v_lshlrev_b32_e32 v20, 16, v22
	v_sub_f32_e32 v20, v20, v45
	v_mul_f32_e32 v20, v46, v20
	v_mul_f32_e32 v20, v20, v50
	v_cvt_pk_bf16_f32 v20, 0, v20
	ds_write_b16_d16_hi v41, v20 offset:33024
	v_and_b32_e32 v20, 0xffff0000, v22
	v_sub_f32_e32 v20, v20, v45
	v_mul_f32_e32 v20, v46, v20
	v_mul_f32_e32 v20, v20, v51
	v_cvt_pk_bf16_f32 v20, 0, v20
	ds_write_b16_d16_hi v41, v20 offset:33088
	v_lshlrev_b32_e32 v20, 16, v23
	v_sub_f32_e32 v22, v20, v45
	v_lshl_add_u64 v[20:21], v[38:39], 2, s[8:9]
	global_load_dwordx4 v[24:27], v[20:21], off offset:16
	global_load_dwordx4 v[74:77], v[20:21], off
	v_mul_f32_e32 v20, v46, v22
	v_mul_f32_e32 v20, v20, v52
	v_cvt_pk_bf16_f32 v20, 0, v20
	ds_write_b16_d16_hi v41, v20 offset:33152
	v_and_b32_e32 v20, 0xffff0000, v23
	v_sub_f32_e32 v20, v20, v45
	v_mul_f32_e32 v20, v46, v20
	v_mul_f32_e32 v20, v20, v53
	v_cvt_pk_bf16_f32 v20, 0, v20
	v_lshl_or_b32 v21, v66, 6, v159
	v_add_u32_e32 v21, v44, v21
	ds_write_b16_d16_hi v21, v20 offset:32768
	v_lshlrev_b32_e32 v20, 16, v16
	v_sub_f32_e32 v20, v20, v45
	v_mul_f32_e32 v20, v46, v20
	v_and_b32_e32 v16, 0xffff0000, v16
	s_waitcnt vmcnt(2)
	v_mul_f32_e32 v20, v20, v70
	v_sub_f32_e32 v16, v16, v45
	v_mul_f32_e32 v16, v46, v16
	v_cvt_pk_bf16_f32 v20, 0, v20
	v_lshl_add_u32 v39, v40, 6, v44
	v_mul_f32_e32 v16, v16, v71
	ds_write_b16_d16_hi v39, v20 offset:32768
	v_cvt_pk_bf16_f32 v16, 0, v16
	ds_write_b16_d16_hi v39, v16 offset:32832
	v_lshlrev_b32_e32 v16, 16, v17
	v_sub_f32_e32 v16, v16, v45
	v_mul_f32_e32 v16, v46, v16
	v_mul_f32_e32 v16, v16, v72
	v_cvt_pk_bf16_f32 v16, 0, v16
	ds_write_b16_d16_hi v39, v16 offset:32896
	v_and_b32_e32 v16, 0xffff0000, v17
	v_sub_f32_e32 v16, v16, v45
	v_mul_f32_e32 v16, v46, v16
	v_mul_f32_e32 v16, v16, v73
	v_cvt_pk_bf16_f32 v16, 0, v16
	ds_write_b16_d16_hi v39, v16 offset:32960
	v_lshlrev_b32_e32 v16, 16, v18
	v_sub_f32_e32 v16, v16, v45
	v_mul_f32_e32 v16, v46, v16
	v_mul_f32_e32 v16, v16, v28
	v_cvt_pk_bf16_f32 v16, 0, v16
	ds_write_b16_d16_hi v39, v16 offset:33024
	v_and_b32_e32 v16, 0xffff0000, v18
	v_sub_f32_e32 v16, v16, v45
	v_mul_f32_e32 v16, v46, v16
	v_mul_f32_e32 v16, v16, v29
	v_cvt_pk_bf16_f32 v16, 0, v16
	ds_write_b16_d16_hi v39, v16 offset:33088
	v_lshlrev_b32_e32 v16, 16, v19
	v_sub_f32_e32 v18, v16, v45
	v_lshl_add_u64 v[16:17], v[36:37], 2, s[8:9]
	global_load_dwordx4 v[20:23], v[16:17], off offset:16
	global_load_dwordx4 v[40:43], v[16:17], off
	v_mul_f32_e32 v16, v46, v18
	v_mul_f32_e32 v16, v16, v30
	v_cvt_pk_bf16_f32 v16, 0, v16
	ds_write_b16_d16_hi v39, v16 offset:33152
	v_and_b32_e32 v16, 0xffff0000, v19
	v_sub_f32_e32 v16, v16, v45
	v_mul_f32_e32 v16, v46, v16
	v_mul_f32_e32 v16, v16, v31
	v_cvt_pk_bf16_f32 v16, 0, v16
	v_lshl_or_b32 v17, v64, 6, v159
	v_add_u32_e32 v17, v44, v17
	ds_write_b16_d16_hi v17, v16 offset:32768
	v_lshlrev_b32_e32 v16, 16, v12
	v_sub_f32_e32 v16, v16, v45
	v_mul_f32_e32 v16, v46, v16
	v_and_b32_e32 v12, 0xffff0000, v12
	s_waitcnt vmcnt(2)
; __device__ __forceinline__ float bflo(unsigned w) { return __uint_as_float(w << 16); }
; __device__ __forceinline__ float bfhi(unsigned w) { return __uint_as_float(w & 0xffff0000u); }
; __device__ void gmlp_item(const Params& p, int layer, int b, int n, int g, char* smem) {
;     ...
; #pragma unroll
;     for (int i = 0; i < 8; ++i) {
;       int q = tid + 256 * i;
;       int st = q & 127, c0 = (q >> 7) * 8;
;       unsigned w[4] = {raw[i].x, raw[i].y, raw[i].z, raw[i].w};
;       float mu = mu_s[st], rs = rs_s[st];
;       const float4* gp = reinterpret_cast<const float4*>(p.gm_gain + (size_t)layer * 512 + g * 128 + c0);
;       float4 g0 = gp[0], g1 = gp[1];
;       float gg[8] = {g0.x, g0.y, g0.z, g0.w, g1.x, g1.y, g1.z, g1.w};
; #pragma unroll
;       for (int e = 0; e < 8; ++e) {
;         float v = (e & 1) ? bfhi(w[e >> 1]) : bflo(w[e >> 1]);
;         float val = (v - mu) * rs * gg[e];
;         *reinterpret_cast<u16*>(smem + 32768 + (st >> 5) * 8192 + (c0 + e) * 64 + (st & 31) * 2) = f2bf(val);
;       }
;     }
	v_mul_f32_e32 v16, v16, v74
	v_sub_f32_e32 v12, v12, v45
	v_mul_f32_e32 v12, v46, v12
	v_cvt_pk_bf16_f32 v16, 0, v16
	v_lshl_add_u32 v37, v38, 6, v44
	v_mul_f32_e32 v12, v12, v75
	ds_write_b16_d16_hi v37, v16 offset:32768
	v_cvt_pk_bf16_f32 v12, 0, v12
	ds_write_b16_d16_hi v37, v12 offset:32832
	v_lshlrev_b32_e32 v12, 16, v13
	v_sub_f32_e32 v12, v12, v45
	v_mul_f32_e32 v12, v46, v12
	v_mul_f32_e32 v12, v12, v76
	v_cvt_pk_bf16_f32 v12, 0, v12
	ds_write_b16_d16_hi v37, v12 offset:32896
	v_and_b32_e32 v12, 0xffff0000, v13
	v_sub_f32_e32 v12, v12, v45
	v_mul_f32_e32 v12, v46, v12
	v_mul_f32_e32 v12, v12, v77
	v_cvt_pk_bf16_f32 v12, 0, v12
	ds_write_b16_d16_hi v37, v12 offset:32960
	v_lshlrev_b32_e32 v12, 16, v14
	v_sub_f32_e32 v12, v12, v45
	v_mul_f32_e32 v12, v46, v12
	v_mul_f32_e32 v12, v12, v24
	v_cvt_pk_bf16_f32 v12, 0, v12
	ds_write_b16_d16_hi v37, v12 offset:33024
	v_and_b32_e32 v12, 0xffff0000, v14
	v_sub_f32_e32 v12, v12, v45
	v_mul_f32_e32 v12, v46, v12
	v_mul_f32_e32 v12, v12, v25
	v_cvt_pk_bf16_f32 v12, 0, v12
	ds_write_b16_d16_hi v37, v12 offset:33088
	v_lshlrev_b32_e32 v12, 16, v15
	v_sub_f32_e32 v14, v12, v45
	v_lshl_add_u64 v[12:13], v[34:35], 2, s[8:9]
	global_load_dwordx4 v[16:19], v[12:13], off offset:16
	global_load_dwordx4 v[28:31], v[12:13], off
	v_mul_f32_e32 v12, v46, v14
	v_mul_f32_e32 v12, v12, v26
	v_cvt_pk_bf16_f32 v12, 0, v12
	ds_write_b16_d16_hi v37, v12 offset:33152
	v_and_b32_e32 v12, 0xffff0000, v15
	v_sub_f32_e32 v12, v12, v45
	v_mul_f32_e32 v12, v46, v12
	v_mul_f32_e32 v12, v12, v27
	v_cvt_pk_bf16_f32 v12, 0, v12
	v_lshl_or_b32 v13, v62, 6, v159
	v_add_u32_e32 v13, v44, v13
	ds_write_b16_d16_hi v13, v12 offset:32768
	v_lshlrev_b32_e32 v12, 16, v8
	v_sub_f32_e32 v12, v12, v45
	v_mul_f32_e32 v12, v46, v12
	v_and_b32_e32 v8, 0xffff0000, v8
	s_waitcnt vmcnt(2)
	v_mul_f32_e32 v12, v12, v40
	v_sub_f32_e32 v8, v8, v45
	v_mul_f32_e32 v8, v46, v8
	v_cvt_pk_bf16_f32 v12, 0, v12
	v_lshl_add_u32 v35, v36, 6, v44
	v_mul_f32_e32 v8, v8, v41
	ds_write_b16_d16_hi v35, v12 offset:32768
	v_cvt_pk_bf16_f32 v8, 0, v8
	ds_write_b16_d16_hi v35, v8 offset:32832
	v_lshlrev_b32_e32 v8, 16, v9
	v_sub_f32_e32 v8, v8, v45
	v_mul_f32_e32 v8, v46, v8
	v_mul_f32_e32 v8, v8, v42
	v_cvt_pk_bf16_f32 v8, 0, v8
	ds_write_b16_d16_hi v35, v8 offset:32896
	v_and_b32_e32 v8, 0xffff0000, v9
	v_sub_f32_e32 v8, v8, v45
	v_mul_f32_e32 v8, v46, v8
	v_mul_f32_e32 v8, v8, v43
	v_cvt_pk_bf16_f32 v8, 0, v8
	ds_write_b16_d16_hi v35, v8 offset:32960
	v_lshlrev_b32_e32 v8, 16, v10
	v_sub_f32_e32 v8, v8, v45
	v_mul_f32_e32 v8, v46, v8
	v_mul_f32_e32 v8, v8, v20
	v_cvt_pk_bf16_f32 v8, 0, v8
	ds_write_b16_d16_hi v35, v8 offset:33024
	v_and_b32_e32 v8, 0xffff0000, v10
	v_sub_f32_e32 v8, v8, v45
	v_mul_f32_e32 v8, v46, v8
	v_mul_f32_e32 v8, v8, v21
	v_cvt_pk_bf16_f32 v10, 0, v8
	v_lshl_add_u64 v[8:9], v[32:33], 2, s[8:9]
	global_load_dwordx4 v[12:15], v[8:9], off offset:16
	global_load_dwordx4 v[24:27], v[8:9], off
	v_lshlrev_b32_e32 v8, 16, v11
	v_sub_f32_e32 v8, v8, v45
	v_mul_f32_e32 v8, v46, v8
	v_mul_f32_e32 v8, v8, v22
	v_cvt_pk_bf16_f32 v8, 0, v8
	ds_write_b16_d16_hi v35, v8 offset:33152
	v_and_b32_e32 v8, 0xffff0000, v11
	v_sub_f32_e32 v8, v8, v45
	v_mul_f32_e32 v8, v46, v8
	v_mul_f32_e32 v8, v8, v23
	v_cvt_pk_bf16_f32 v8, 0, v8
	v_lshl_or_b32 v9, v60, 6, v159
	v_add_u32_e32 v9, v44, v9
	ds_write_b16_d16_hi v35, v10 offset:33088
	ds_write_b16_d16_hi v9, v8 offset:32768
	v_lshlrev_b32_e32 v8, 16, v4
	v_sub_f32_e32 v8, v8, v45
	v_mul_f32_e32 v8, v46, v8
	v_and_b32_e32 v4, 0xffff0000, v4
	s_waitcnt vmcnt(2)
	v_mul_f32_e32 v8, v8, v28
	v_sub_f32_e32 v4, v4, v45
	v_mul_f32_e32 v4, v46, v4
	v_cvt_pk_bf16_f32 v8, 0, v8
	v_lshl_add_u32 v9, v34, 6, v44
	v_mul_f32_e32 v4, v4, v29
	ds_write_b16_d16_hi v9, v8 offset:32768
	v_cvt_pk_bf16_f32 v4, 0, v4
	ds_write_b16_d16_hi v9, v4 offset:32832
	v_lshlrev_b32_e32 v4, 16, v5
	v_sub_f32_e32 v4, v4, v45
	v_mul_f32_e32 v4, v46, v4
	v_mul_f32_e32 v4, v4, v30
	v_cvt_pk_bf16_f32 v4, 0, v4
	ds_write_b16_d16_hi v9, v4 offset:32896
	v_and_b32_e32 v4, 0xffff0000, v5
	v_sub_f32_e32 v4, v4, v45
	v_mul_f32_e32 v4, v46, v4
	v_mul_f32_e32 v4, v4, v31
	v_cvt_pk_bf16_f32 v4, 0, v4
	ds_write_b16_d16_hi v9, v4 offset:32960
	v_lshlrev_b32_e32 v4, 16, v6
	v_sub_f32_e32 v4, v4, v45
	v_mul_f32_e32 v4, v46, v4
	v_mul_f32_e32 v4, v4, v16
	v_cvt_pk_bf16_f32 v4, 0, v4
	ds_write_b16_d16_hi v9, v4 offset:33024
	v_and_b32_e32 v4, 0xffff0000, v6
	v_sub_f32_e32 v4, v4, v45
	v_mul_f32_e32 v4, v46, v4
	v_mul_f32_e32 v4, v4, v17
	v_cvt_pk_bf16_f32 v4, 0, v4
	ds_write_b16_d16_hi v9, v4 offset:33088
	v_lshlrev_b32_e32 v4, 16, v7
	v_sub_f32_e32 v4, v4, v45
	v_mul_f32_e32 v4, v46, v4
	v_mul_f32_e32 v4, v4, v18
	v_cvt_pk_bf16_f32 v4, 0, v4
	ds_write_b16_d16_hi v9, v4 offset:33152
	v_and_b32_e32 v4, 0xffff0000, v7
	v_sub_f32_e32 v4, v4, v45
	v_mul_f32_e32 v4, v46, v4
	v_mul_f32_e32 v4, v4, v19
	v_cvt_pk_bf16_f32 v4, 0, v4
	v_lshl_or_b32 v5, v58, 6, v159
	v_add_u32_e32 v5, v44, v5
	ds_write_b16_d16_hi v5, v4 offset:32768
	v_lshlrev_b32_e32 v4, 16, v0
	v_sub_f32_e32 v4, v4, v45
	v_mul_f32_e32 v4, v46, v4
	v_and_b32_e32 v0, 0xffff0000, v0
	s_waitcnt vmcnt(0)
	v_mul_f32_e32 v4, v4, v24
	v_sub_f32_e32 v0, v0, v45
	v_mul_f32_e32 v0, v46, v0
	v_cvt_pk_bf16_f32 v4, 0, v4
	v_lshl_add_u32 v5, v32, 6, v44
	v_mul_f32_e32 v0, v0, v25
	ds_write_b16_d16_hi v5, v4 offset:32768
	v_cvt_pk_bf16_f32 v0, 0, v0
	ds_write_b16_d16_hi v5, v0 offset:32832
	v_lshlrev_b32_e32 v0, 16, v1
	v_sub_f32_e32 v0, v0, v45
	v_mul_f32_e32 v0, v46, v0
	v_mul_f32_e32 v0, v0, v26
	v_cvt_pk_bf16_f32 v0, 0, v0
	ds_write_b16_d16_hi v5, v0 offset:32896
	v_and_b32_e32 v0, 0xffff0000, v1
	v_sub_f32_e32 v0, v0, v45
	v_mul_f32_e32 v0, v46, v0
	v_mul_f32_e32 v0, v0, v27
	v_cvt_pk_bf16_f32 v0, 0, v0
	ds_write_b16_d16_hi v5, v0 offset:32960
	v_lshlrev_b32_e32 v0, 16, v2
	v_sub_f32_e32 v0, v0, v45
	v_mul_f32_e32 v0, v46, v0
	v_mul_f32_e32 v0, v0, v12
	v_cvt_pk_bf16_f32 v0, 0, v0
	ds_write_b16_d16_hi v5, v0 offset:33024
	v_and_b32_e32 v0, 0xffff0000, v2
	v_sub_f32_e32 v0, v0, v45
	v_mul_f32_e32 v0, v46, v0
	v_mul_f32_e32 v0, v0, v13
	v_cvt_pk_bf16_f32 v0, 0, v0
	ds_write_b16_d16_hi v5, v0 offset:33088
	v_lshlrev_b32_e32 v0, 16, v3
	v_sub_f32_e32 v0, v0, v45
	v_mul_f32_e32 v0, v46, v0
	v_mul_f32_e32 v0, v0, v14
	v_cvt_pk_bf16_f32 v0, 0, v0
	ds_write_b16_d16_hi v5, v0 offset:33152
	v_and_b32_e32 v0, 0xffff0000, v3
	v_sub_f32_e32 v0, v0, v45
	v_mul_f32_e32 v0, v46, v0
	v_mul_f32_e32 v0, v0, v15
	s_lshl_b32 s8, s12, 15
	v_cvt_pk_bf16_f32 v0, 0, v0
	v_lshl_or_b32 v1, v56, 6, v159
	s_add_u32 s8, s13, s8
	v_add_u32_e32 v1, v44, v1
	s_addc_u32 s9, s42, 0
	v_lshlrev_b32_e32 v3, 4, v59
	ds_write_b16_d16_hi v1, v0 offset:32768
	v_lshl_add_u64 v[0:1], s[8:9], 0, v[128:129]
	v_lshlrev_b32_e32 v2, 11, v59
	v_and_b32_e32 v3, 48, v3
	v_lshl_add_u64 v[0:1], v[0:1], 0, s[24:25]
	v_and_or_b32 v2, v2, s53, v3
	s_mov_b32 s8, 0
; #define MFMA16(a, b, c) __builtin_amdgcn_mfma_f32_16x16x32_bf16(a, b, c, 0, 0, 0)
; __device__ void gmlp_item(const Params& p, int layer, int b, int n, int g, char* smem) {
;     ...
; #pragma unroll 2
;   for (int i = 0; i < 8; ++i) {
;     int q = tid + 256 * i;
;     int t = q >> 4, cch = q & 15;
;     uint4 v = *reinterpret_cast<const uint4*>(Ws + (size_t)g * 16384 + t * 128 + cch * 8);
;     *reinterpret_cast<uint4*>(smem + (cch >> 2) * 8192 + t * 64 + (cch & 3) * 16) = v;
;   }
;   __syncthreads();
;   f32x4 acc[4][4];
; #pragma unroll
;   for (int m = 0; m < 4; ++m)
; #pragma unroll
;     for (int nn = 0; nn < 4; ++nn) acc[m][nn] = f32x4{0.f, 0.f, 0.f, 0.f};
; #pragma unroll
;   for (int ks = 0; ks < 4; ++ks) {
;     bf16x8 a[4], bb[4];
; #pragma unroll
;     for (int m = 0; m < 4; ++m)
;       a[m] = *reinterpret_cast<const bf16x8*>(smem + ks * 8192 + (wr * 64 + m * 16 + fr) * 64 + fq * 16);
; #pragma unroll
;     for (int nn = 0; nn < 4; ++nn)
;       bb[nn] = *reinterpret_cast<const bf16x8*>(smem + 32768 + ks * 8192 + (wc * 64 + nn * 16 + fr) * 64 + fq * 16);
; #pragma unroll
;     for (int m = 0; m < 4; ++m)
; #pragma unroll
;       for (int nn = 0; nn < 4; ++nn) acc[m][nn] = MFMA16(a[m], bb[nn], acc[m][nn]);
.LBB0_1122:
	v_add_u32_e32 v3, s8, v59
	v_ashrrev_i32_e32 v12, 4, v3
	v_add_u32_e32 v3, 0x100, v3
	v_ashrrev_i32_e32 v3, 4, v3
	v_lshlrev_b32_e32 v4, 7, v12
	v_lshlrev_b32_e32 v6, 7, v3
	v_ashrrev_i32_e32 v5, 31, v4
	v_ashrrev_i32_e32 v7, 31, v6
	v_lshl_add_u64 v[4:5], v[4:5], 1, v[0:1]
	v_lshl_add_u64 v[8:9], v[6:7], 1, v[0:1]
	global_load_dwordx4 v[4:7], v[4:5], off
	s_nop 0
	global_load_dwordx4 v[8:11], v[8:9], off
	s_addk_i32 s8, 0x200
	s_cmpk_lg_i32 s8, 0x800
	v_lshl_add_u32 v12, v12, 6, v2
	v_lshl_add_u32 v3, v3, 6, v2
	s_waitcnt vmcnt(1)
	ds_write_b128 v12, v[4:7]
	s_waitcnt vmcnt(0)
	ds_write_b128 v3, v[8:11]
	s_cbranch_scc1 .LBB0_1122
	v_bfe_u32 v54, v59, 4, 2
	v_ashrrev_i32_e32 v55, 7, v59
	v_lshlrev_b32_e32 v4, 4, v54
	v_lshlrev_b32_e32 v0, 12, v55
	v_lshlrev_b32_e32 v5, 6, v49
	v_or3_b32 v57, v4, v0, v5
	s_waitcnt lgkmcnt(0)
	s_barrier
	ds_read_b128 v[0:3], v57
	v_bfe_u32 v61, v59, 6, 1
	v_lshlrev_b32_e32 v6, 12, v61
	v_or3_b32 v63, v4, v6, v5
	ds_read_b128 v[4:7], v63 offset:32768
	ds_read_b128 v[8:11], v57 offset:1024
	ds_read_b128 v[12:15], v63 offset:33792
	ds_read_b128 v[24:27], v63 offset:34816
	ds_read_b128 v[28:31], v63 offset:35840
	s_waitcnt lgkmcnt(4)
	v_mfma_f32_16x16x32_bf16 v[16:19], v[0:3], v[4:7], 0
	s_ashr_i32 s8, s11, 31
	s_add_u32 s11, s28, s11
	s_addc_u32 s12, s29, s8
	s_waitcnt lgkmcnt(2)
	v_mfma_f32_16x16x32_bf16 v[20:23], v[0:3], v[12:15], 0
	s_lshl_b32 s8, s10, 2
	s_add_u32 s8, s20, s8
	v_lshlrev_b32_e32 v55, 6, v55
	s_waitcnt lgkmcnt(1)
	v_mfma_f32_16x16x32_bf16 v[36:39], v[0:3], v[24:27], 0
	s_addc_u32 s9, s21, 0
	v_lshl_or_b32 v54, v54, 2, v55
	s_add_u32 s8, s8, 0x1800
	s_waitcnt lgkmcnt(0)
	v_mfma_f32_16x16x32_bf16 v[40:43], v[0:3], v[28:31], 0
	s_addc_u32 s9, s9, 0
	v_ashrrev_i32_e32 v55, 31, v54
	v_lshl_add_u64 v[126:127], v[54:55], 2, s[8:9]
	v_mfma_f32_16x16x32_bf16 v[44:47], v[8:11], v[4:7], 0
	v_or_b32_e32 v130, 32, v54
	v_ashrrev_i32_e32 v131, 31, v130
	v_lshlrev_b32_e32 v49, 2, v49
	v_mfma_f32_16x16x32_bf16 v[50:53], v[8:11], v[12:15], 0
	v_lshl_add_u64 v[130:131], v[130:131], 2, s[8:9]
	v_ashrrev_i32_e32 v69, 31, v68
	v_ashrrev_i32_e32 v67, 31, v66
	v_mfma_f32_16x16x32_bf16 v[70:73], v[8:11], v[24:27], 0
	v_ashrrev_i32_e32 v65, 31, v64
	v_mfma_f32_16x16x32_bf16 v[74:77], v[8:11], v[28:31], 0
	ds_read_b128 v[0:3], v57 offset:2048
	ds_read_b128 v[8:11], v57 offset:3072
	s_waitcnt lgkmcnt(1)
	v_mfma_f32_16x16x32_bf16 v[82:85], v[0:3], v[12:15], 0
	s_waitcnt lgkmcnt(0)
	v_mfma_f32_16x16x32_bf16 v[98:101], v[8:11], v[12:15], 0
	ds_read_b128 v[12:15], v57 offset:8192
	v_mfma_f32_16x16x32_bf16 v[78:81], v[0:3], v[4:7], 0
	v_mfma_f32_16x16x32_bf16 v[86:89], v[0:3], v[24:27], 0
	v_mfma_f32_16x16x32_bf16 v[94:97], v[8:11], v[4:7], 0
	v_mfma_f32_16x16x32_bf16 v[32:35], v[8:11], v[24:27], 0
	ds_read_b128 v[102:105], v63 offset:40960
	ds_read_b128 v[24:27], v57 offset:9216
	ds_read_b128 v[106:109], v63 offset:41984
	ds_read_b128 v[118:121], v63 offset:43008
	ds_read_b128 v[4:7], v63 offset:44032
	v_mfma_f32_16x16x32_bf16 v[90:93], v[0:3], v[28:31], 0
	s_waitcnt lgkmcnt(4)
	v_mfma_f32_16x16x32_bf16 v[110:113], v[12:15], v[102:105], v[16:19]
	s_waitcnt lgkmcnt(2)
	v_mfma_f32_16x16x32_bf16 v[114:117], v[12:15], v[106:109], v[20:23]
	s_waitcnt lgkmcnt(1)
	v_mfma_f32_16x16x32_bf16 v[122:125], v[12:15], v[118:121], v[36:39]
	s_waitcnt lgkmcnt(0)
	v_mfma_f32_16x16x32_bf16 v[134:137], v[12:15], v[4:7], v[40:43]
	ds_read_b128 v[146:149], v57 offset:10240
	ds_read_b128 v[12:15], v57 offset:11264
	v_mfma_f32_16x16x32_bf16 v[0:3], v[8:11], v[28:31], 0
	ds_read_b128 v[150:153], v57 offset:16384
	ds_read_b128 v[162:165], v57 offset:17408
	ds_read_b128 v[166:169], v57 offset:18432
	ds_read_b128 v[8:11], v57 offset:19456
	ds_read_b128 v[36:39], v63 offset:49152
	ds_read_b128 v[28:31], v63 offset:50176
	ds_read_b128 v[20:23], v63 offset:51200
	ds_read_b128 v[16:19], v63 offset:52224
	v_mfma_f32_16x16x32_bf16 v[138:141], v[24:27], v[102:105], v[44:47]
	v_mfma_f32_16x16x32_bf16 v[50:53], v[24:27], v[106:109], v[50:53]
	v_mfma_f32_16x16x32_bf16 v[70:73], v[24:27], v[118:121], v[70:73]
	v_mfma_f32_16x16x32_bf16 v[74:77], v[24:27], v[4:7], v[74:77]
	ds_read_b128 v[170:173], v57 offset:24576
	ds_read_b128 v[174:177], v57 offset:25600
	ds_read_b128 v[178:181], v57 offset:26624
	ds_read_b128 v[24:27], v57 offset:27648
	ds_read_b128 v[182:185], v63 offset:57344
	ds_read_b128 v[186:189], v63 offset:58368
	ds_read_b128 v[44:47], v63 offset:59392
	ds_read_b128 v[40:43], v63 offset:60416
	s_waitcnt lgkmcnt(0)
	v_mfma_f32_16x16x32_bf16 v[78:81], v[146:149], v[102:105], v[78:81]
	s_barrier
; #define MFMA16(a, b, c) __builtin_amdgcn_mfma_f32_16x16x32_bf16(a, b, c, 0, 0, 0)
; __device__ void gmlp_item(const Params& p, int layer, int b, int n, int g, char* smem) {
;     ...
;   for (int ks = 0; ks < 4; ++ks) {
;     bf16x8 a[4], bb[4];
; #pragma unroll
;     for (int m = 0; m < 4; ++m)
;       a[m] = *reinterpret_cast<const bf16x8*>(smem + ks * 8192 + (wr * 64 + m * 16 + fr) * 64 + fq * 16);
; #pragma unroll
;     for (int nn = 0; nn < 4; ++nn)
;       bb[nn] = *reinterpret_cast<const bf16x8*>(smem + 32768 + ks * 8192 + (wc * 64 + nn * 16 + fr) * 64 + fq * 16);
; #pragma unroll
;     for (int m = 0; m < 4; ++m)
; #pragma unroll
;       for (int nn = 0; nn < 4; ++nn) acc[m][nn] = MFMA16(a[m], bb[nn], acc[m][nn]);
;   }
;   __syncthreads();
;   {
;     float* Tf = reinterpret_cast<float*>(smem);
; #pragma unroll
;     for (int m = 0; m < 4; ++m)
; #pragma unroll
;       for (int j = 0; j < 4; ++j) {
;         int t = wr * 64 + m * 16 + fq * 4 + j;
;         float bias = p.gm_b_s[(size_t)layer * 512 + g * 128 + t];
; #pragma unroll
;         for (int nn = 0; nn < 4; ++nn) Tf[t * 132 + wc * 64 + nn * 16 + fr] = acc[m][nn][j] + bias;
	global_load_dwordx4 v[190:193], v[130:131], off
	v_mfma_f32_16x16x32_bf16 v[82:85], v[146:149], v[106:109], v[82:85]
	v_ashrrev_i32_e32 v63, 31, v62
	v_mfma_f32_16x16x32_bf16 v[86:89], v[146:149], v[118:121], v[86:89]
	v_mfma_f32_16x16x32_bf16 v[90:93], v[146:149], v[4:7], v[90:93]
	global_load_dwordx4 v[146:149], v[126:127], off
	v_or_b32_e32 v126, 16, v54
	v_ashrrev_i32_e32 v127, 31, v126
	v_lshl_add_u64 v[126:127], v[126:127], 2, s[8:9]
	v_mfma_f32_16x16x32_bf16 v[110:113], v[150:153], v[36:39], v[110:113]
	v_mfma_f32_16x16x32_bf16 v[114:117], v[150:153], v[28:31], v[114:117]
	v_mfma_f32_16x16x32_bf16 v[122:125], v[150:153], v[20:23], v[122:125]
	v_mfma_f32_16x16x32_bf16 v[134:137], v[150:153], v[16:19], v[134:137]
	global_load_dwordx4 v[150:153], v[126:127], off
	v_lshl_or_b32 v126, v61, 8, v49
	v_mad_u64_u32 v[126:127], s[42:43], v54, s55, v[126:127]
	v_mfma_f32_16x16x32_bf16 v[110:113], v[170:173], v[182:185], v[110:113]
	v_add_u32_e32 v57, 0x400, v126
	v_or_b32_e32 v54, 48, v54
	v_ashrrev_i32_e32 v61, 31, v60
	v_mfma_f32_16x16x32_bf16 v[114:117], v[170:173], v[186:189], v[114:117]
	v_mfma_f32_16x16x32_bf16 v[122:125], v[170:173], v[44:47], v[122:125]
	s_waitcnt vmcnt(1)
	s_nop 1
	v_add_f32_e32 v49, v110, v146
	v_mfma_f32_16x16x32_bf16 v[134:137], v[170:173], v[40:43], v[134:137]
	s_nop 1
	v_add_f32_e32 v55, v114, v146
	ds_write2_b32 v126, v49, v55 offset1:16
	v_add_f32_e32 v49, v122, v146
	v_mfma_f32_16x16x32_bf16 v[98:101], v[12:15], v[106:109], v[98:101]
	v_mfma_f32_16x16x32_bf16 v[94:97], v[12:15], v[102:105], v[94:97]
	s_nop 0
	v_add_f32_e32 v55, v134, v146
	ds_write2_b32 v126, v49, v55 offset0:32 offset1:48
	v_add_f32_e32 v49, v111, v147
	v_add_f32_e32 v55, v115, v147
	ds_write2_b32 v126, v49, v55 offset0:132 offset1:148
	v_add_f32_e32 v49, v123, v147
	v_add_f32_e32 v55, v135, v147
	ds_write2_b32 v126, v49, v55 offset0:164 offset1:180
	v_add_f32_e32 v49, v112, v148
	v_add_f32_e32 v55, v116, v148
	ds_write2_b32 v57, v49, v55 offset0:8 offset1:24
	v_add_f32_e32 v49, v124, v148
	v_add_f32_e32 v55, v136, v148
	ds_write2_b32 v57, v49, v55 offset0:40 offset1:56
	v_add_f32_e32 v49, v113, v149
	v_add_f32_e32 v55, v117, v149
	ds_write2_b32 v57, v49, v55 offset0:140 offset1:156
	v_add_f32_e32 v49, v125, v149
	v_add_f32_e32 v55, v137, v149
	ds_write2_b32 v57, v49, v55 offset0:172 offset1:188
	v_ashrrev_i32_e32 v55, 31, v54
	v_lshl_add_u64 v[54:55], v[54:55], 2, s[8:9]
	global_load_dwordx4 v[106:109], v[54:55], off
	v_mfma_f32_16x16x32_bf16 v[102:105], v[162:165], v[36:39], v[138:141]
	v_add_u32_e32 v54, 0x2000, v126
	v_ashrrev_i32_e32 v57, 31, v56
	v_mfma_f32_16x16x32_bf16 v[50:53], v[162:165], v[28:31], v[50:53]
	v_mfma_f32_16x16x32_bf16 v[70:73], v[162:165], v[20:23], v[70:73]
	v_mfma_f32_16x16x32_bf16 v[74:77], v[162:165], v[16:19], v[74:77]
	v_mfma_f32_16x16x32_bf16 v[102:105], v[174:177], v[182:185], v[102:105]
	v_mfma_f32_16x16x32_bf16 v[50:53], v[174:177], v[186:189], v[50:53]
	v_mfma_f32_16x16x32_bf16 v[70:73], v[174:177], v[44:47], v[70:73]
	s_waitcnt vmcnt(1)
	s_nop 4
	v_add_f32_e32 v49, v102, v150
	v_add_f32_e32 v50, v50, v150
	ds_write2_b32 v54, v49, v50 offset0:64 offset1:80
	v_mfma_f32_16x16x32_bf16 v[74:77], v[174:177], v[40:43], v[74:77]
	v_add_f32_e32 v55, v53, v153
	v_add_f32_e32 v49, v70, v150
	v_mfma_f32_16x16x32_bf16 v[78:81], v[166:169], v[36:39], v[78:81]
	v_mfma_f32_16x16x32_bf16 v[82:85], v[166:169], v[28:31], v[82:85]
	s_nop 3
	v_add_f32_e32 v50, v74, v150
	ds_write2_b32 v54, v49, v50 offset0:96 offset1:112
	v_add_f32_e32 v49, v103, v151
	v_add_f32_e32 v50, v51, v151
	ds_write2_b32 v54, v49, v50 offset0:196 offset1:212
	v_add_f32_e32 v49, v71, v151
	v_add_f32_e32 v50, v75, v151
	ds_write2_b32 v54, v49, v50 offset0:228 offset1:244
	v_add_f32_e32 v49, v104, v152
	v_add_f32_e32 v50, v52, v152
	v_add_u32_e32 v54, 0x2400, v126
	v_mfma_f32_16x16x32_bf16 v[86:89], v[166:169], v[20:23], v[86:89]
	ds_write2_b32 v54, v49, v50 offset0:72 offset1:88
	v_add_f32_e32 v49, v72, v152
	v_add_f32_e32 v50, v76, v152
	v_mfma_f32_16x16x32_bf16 v[90:93], v[166:169], v[16:19], v[90:93]
	ds_write2_b32 v54, v49, v50 offset0:104 offset1:120
	v_add_f32_e32 v49, v105, v153
	ds_write2_b32 v54, v49, v55 offset0:204 offset1:220
	v_mfma_f32_16x16x32_bf16 v[50:53], v[178:181], v[182:185], v[78:81]
	v_add_f32_e32 v49, v73, v153
	v_add_f32_e32 v55, v77, v153
	ds_write2_b32 v54, v49, v55 offset0:236 offset1:252
	v_mfma_f32_16x16x32_bf16 v[70:73], v[178:181], v[186:189], v[82:85]
	v_add_u32_e32 v54, 0x4000, v126
	s_nop 2
	v_add_f32_e32 v49, v50, v190
	v_mfma_f32_16x16x32_bf16 v[74:77], v[178:181], v[44:47], v[86:89]
	v_mfma_f32_16x16x32_bf16 v[78:81], v[178:181], v[40:43], v[90:93]
	s_nop 0
	v_add_f32_e32 v50, v70, v190
	ds_write2_b32 v54, v49, v50 offset0:128 offset1:144
	s_nop 3
	v_add_f32_e32 v49, v74, v190
	v_mfma_f32_16x16x32_bf16 v[32:35], v[12:15], v[118:121], v[32:35]
	v_mfma_f32_16x16x32_bf16 v[0:3], v[12:15], v[4:7], v[0:3]
	v_add_f32_e32 v50, v78, v190
	ds_write2_b32 v54, v49, v50 offset0:160 offset1:176
	v_add_f32_e32 v49, v51, v191
	v_add_f32_e32 v4, v71, v191
	v_add_u32_e32 v50, 0x4400, v126
	v_add_f32_e32 v12, v75, v191
	v_add_f32_e32 v13, v79, v191
	ds_write2_b32 v50, v49, v4 offset0:4 offset1:20
	v_mfma_f32_16x16x32_bf16 v[4:7], v[8:11], v[36:39], v[94:97]
	ds_write2_b32 v50, v12, v13 offset0:36 offset1:52
	v_ashrrev_i32_e32 v49, 31, v48
	v_lshl_add_u64 v[70:71], v[56:57], 0, s[16:17]
	v_mfma_f32_16x16x32_bf16 v[12:15], v[8:11], v[28:31], v[98:101]
	v_add_f32_e32 v28, v52, v192
	v_add_f32_e32 v29, v72, v192
	ds_write2_b32 v50, v28, v29 offset0:136 offset1:152
	v_mfma_f32_16x16x32_bf16 v[20:23], v[8:11], v[20:23], v[32:35]
	v_add_f32_e32 v28, v76, v192
	v_add_f32_e32 v29, v80, v192
	ds_write2_b32 v50, v28, v29 offset0:168 offset1:184
	v_mfma_f32_16x16x32_bf16 v[0:3], v[8:11], v[16:19], v[0:3]
	v_add_f32_e32 v8, v53, v193
	v_add_f32_e32 v9, v73, v193
	v_add_u32_e32 v16, 0x4800, v126
	v_mfma_f32_16x16x32_bf16 v[4:7], v[24:27], v[182:185], v[4:7]
	ds_write2_b32 v16, v8, v9 offset0:12 offset1:28
	v_add_f32_e32 v17, v77, v193
	v_add_f32_e32 v18, v81, v193
	v_mfma_f32_16x16x32_bf16 v[8:11], v[24:27], v[186:189], v[12:15]
	ds_write2_b32 v16, v17, v18 offset0:44 offset1:60
	s_waitcnt vmcnt(0)
; __device__ __forceinline__ unsigned pack2(float a, float b) { return (unsigned)f2bf(a) | ((unsigned)f2bf(b) << 16); }
; __device__ __forceinline__ float bflo(unsigned w) { return __uint_as_float(w << 16); }
; __device__ __forceinline__ float bfhi(unsigned w) { return __uint_as_float(w & 0xffff0000u); }
; __device__ __forceinline__ float silu_f(float g) { return g / (1.f + __expf(-g)); }
; __device__ void gmlp_item(const Params& p, int layer, int b, int n, int g, char* smem) {
;     ...
;   {
;     float* Tf = reinterpret_cast<float*>(smem);
; #pragma unroll
;     for (int m = 0; m < 4; ++m)
; #pragma unroll
;       for (int j = 0; j < 4; ++j) {
;         int t = wr * 64 + m * 16 + fq * 4 + j;
;         float bias = p.gm_b_s[(size_t)layer * 512 + g * 128 + t];
; #pragma unroll
;         for (int nn = 0; nn < 4; ++nn) Tf[t * 132 + wc * 64 + nn * 16 + fr] = acc[m][nn][j] + bias;
;       }
;     __syncthreads();
;     uint4 uu[8], gt[8];
; #pragma unroll
;     for (int i = 0; i < 8; ++i) {
;       int q = tid + 256 * i, t = q >> 4, c = (q & 15) * 8;
;       uu[i] = *reinterpret_cast<const uint4*>(P + (t0 + t) * NP + g * 128 + c);
;       gt[i] = *reinterpret_cast<const uint4*>(P + (t0 + t) * NP + 1024 + g * 128 + c);
;     }
; #pragma unroll
;     for (int i = 0; i < 8; ++i) {
;       int q = tid + 256 * i, t = q >> 4, c = (q & 15) * 8;
;       float4 m0 = *reinterpret_cast<const float4*>(Tf + t * 132 + c);
;       float4 m1 = *reinterpret_cast<const float4*>(Tf + t * 132 + c + 4);
;       float mm[8] = {m0.x, m0.y, m0.z, m0.w, m1.x, m1.y, m1.z, m1.w};
;       unsigned uw[4] = {uu[i].x, uu[i].y, uu[i].z, uu[i].w};
;       unsigned gw[4] = {gt[i].x, gt[i].y, gt[i].z, gt[i].w};
;       unsigned ow[4];
; #pragma unroll
;       for (int e = 0; e < 4; ++e) {
;         float y0 = bflo(uw[e]) * mm[2 * e] * silu_f(bflo(gw[e]));
;         float y1 = bfhi(uw[e]) * mm[2 * e + 1] * silu_f(bfhi(gw[e]));
;         ow[e] = pack2(y0, y1);
;       }
;       *reinterpret_cast<uint4*>(Y + (t0 + t) * YW + g * 128 + c) = make_uint4(ow[0], ow[1], ow[2], ow[3]);
	s_nop 1
	v_add_f32_e32 v4, v4, v106
	v_add_u32_e32 v16, 0x6000, v126
	v_mfma_f32_16x16x32_bf16 v[12:15], v[24:27], v[44:47], v[20:23]
	v_lshl_add_u64 v[36:37], v[62:63], 0, s[16:17]
	v_add_f32_e32 v8, v8, v106
	ds_write2_b32 v16, v4, v8 offset0:192 offset1:208
	v_mfma_f32_16x16x32_bf16 v[0:3], v[24:27], v[40:43], v[0:3]
	v_lshl_add_u64 v[20:21], v[64:65], 0, s[16:17]
	s_nop 2
	v_add_f32_e32 v4, v12, v106
	v_lshl_add_u64 v[38:39], v[60:61], 0, s[16:17]
	s_nop 1
	v_add_f32_e32 v0, v0, v106
	ds_write2_b32 v16, v4, v0 offset0:224 offset1:240
	v_add_f32_e32 v0, v5, v107
	v_add_f32_e32 v4, v9, v107
	v_add_u32_e32 v5, 0x6400, v126
	ds_write2_b32 v5, v0, v4 offset0:68 offset1:84
	v_add_f32_e32 v0, v13, v107
	v_add_f32_e32 v1, v1, v107
	ds_write2_b32 v5, v0, v1 offset0:100 offset1:116
	v_add_f32_e32 v0, v6, v108
	v_add_f32_e32 v1, v10, v108
	ds_write2_b32 v5, v0, v1 offset0:200 offset1:216
	v_add_f32_e32 v0, v14, v108
	v_add_f32_e32 v1, v2, v108
	ds_write2_b32 v5, v0, v1 offset0:232 offset1:248
	v_add_f32_e32 v0, v7, v109
	v_add_f32_e32 v1, v11, v109
	v_add_u32_e32 v2, 0x6800, v126
	ds_write2_b32 v2, v0, v1 offset0:76 offset1:92
	v_add_f32_e32 v0, v15, v109
	v_add_f32_e32 v1, v3, v109
	ds_write2_b32 v2, v0, v1 offset0:108 offset1:124
	v_lshlrev_b32_e32 v0, 3, v59
	v_lshl_add_u64 v[8:9], v[48:49], 0, s[16:17]
	v_mov_b64_e32 v[10:11], s[6:7]
	v_and_b32_e32 v24, 0x78, v0
	v_mad_u64_u32 v[0:1], s[6:7], v8, s39, v[10:11]
	v_mad_i32_i24 v1, v9, s39, v1
	s_lshl_b32 s6, s10, 1
	s_mov_b32 s7, s17
	v_lshl_add_u64 v[0:1], v[0:1], 0, s[6:7]
	v_lshlrev_b32_e32 v128, 1, v24
	v_lshl_add_u64 v[12:13], v[68:69], 0, s[16:17]
	v_lshl_add_u64 v[52:53], v[0:1], 0, v[128:129]
	v_mad_u64_u32 v[0:1], s[8:9], v12, s39, v[10:11]
	v_mad_i32_i24 v1, v13, s39, v1
	v_lshl_add_u64 v[0:1], v[0:1], 0, s[6:7]
	v_lshl_add_u64 v[32:33], v[0:1], 0, v[128:129]
	v_mad_u64_u32 v[0:1], s[8:9], v70, s39, v[10:11]
	v_mad_i32_i24 v1, v71, s39, v1
	v_lshl_add_u64 v[0:1], v[0:1], 0, s[6:7]
	v_lshl_add_u64 v[4:5], v[0:1], 0, v[128:129]
	s_waitcnt lgkmcnt(0)
	s_barrier
	global_load_dwordx4 v[0:3], v[4:5], off
	s_nop 0
	global_load_dwordx4 v[4:7], v[4:5], off offset:2048
	v_lshl_add_u64 v[16:17], v[66:67], 0, s[16:17]
	v_mad_u64_u32 v[14:15], s[8:9], v16, s39, v[10:11]
	v_mad_i32_i24 v15, v17, s39, v15
	v_lshl_add_u64 v[14:15], v[14:15], 0, s[6:7]
	v_lshl_add_u64 v[30:31], v[14:15], 0, v[128:129]
	v_mad_u64_u32 v[14:15], s[8:9], v20, s39, v[10:11]
	v_mad_i32_i24 v15, v21, s39, v15
	v_lshl_add_u64 v[14:15], v[14:15], 0, s[6:7]
	v_lshl_add_u64 v[26:27], v[14:15], 0, v[128:129]
	v_mad_u64_u32 v[14:15], s[8:9], v36, s39, v[10:11]
	v_mad_i32_i24 v15, v37, s39, v15
	v_ashrrev_i32_e32 v59, 31, v58
	v_lshl_add_u64 v[14:15], v[14:15], 0, s[6:7]
	v_lshl_add_u64 v[72:73], v[58:59], 0, s[16:17]
	v_lshl_add_u64 v[22:23], v[14:15], 0, v[128:129]
	v_mad_u64_u32 v[14:15], s[8:9], v38, s39, v[10:11]
	v_mad_u64_u32 v[10:11], s[8:9], v72, s39, v[10:11]
	v_mad_i32_i24 v15, v39, s39, v15
	v_mad_i32_i24 v11, v73, s39, v11
	v_lshl_add_u64 v[14:15], v[14:15], 0, s[6:7]
	v_lshl_add_u64 v[10:11], v[10:11], 0, s[6:7]
	s_add_u32 s6, s11, s6
	s_addc_u32 s7, s12, 0
	v_lshl_add_u64 v[18:19], v[14:15], 0, v[128:129]
	v_lshl_add_u64 v[14:15], v[10:11], 0, v[128:129]
	v_lshlrev_b32_e32 v10, 2, v24
	v_lshl_add_u64 v[24:25], s[6:7], 0, v[128:129]
	v_lshl_add_u64 v[74:75], v[24:25], 0, s[26:27]
	v_mad_u64_u32 v[54:55], s[6:7], v48, s55, v[10:11]
	v_mad_u64_u32 v[48:49], s[6:7], v12, s63, v[74:75]
	v_mad_u64_u32 v[46:47], s[6:7], v16, s63, v[74:75]
	v_mad_u64_u32 v[50:51], s[6:7], v8, s63, v[74:75]
	v_mad_i32_i24 v49, v13, s63, v49
	v_mad_i32_i24 v47, v17, s63, v47
	v_mad_u64_u32 v[44:45], s[6:7], v20, s63, v[74:75]
	v_mad_u64_u32 v[16:17], s[6:7], v60, s55, v[10:11]
	v_mad_u64_u32 v[12:13], s[6:7], v58, s55, v[10:11]
	v_mad_i32_i24 v51, v9, s63, v51
	v_mad_i32_i24 v45, v21, s63, v45
	v_mad_u64_u32 v[20:21], s[6:7], v62, s55, v[10:11]
	v_mad_u64_u32 v[8:9], s[6:7], v56, s55, v[10:11]
	v_mad_u64_u32 v[28:29], s[6:7], v66, s55, v[10:11]
	v_mad_u64_u32 v[34:35], s[6:7], v68, s55, v[10:11]
	v_mad_u64_u32 v[24:25], s[6:7], v64, s55, v[10:11]
	v_mad_u64_u32 v[42:43], s[6:7], v36, s63, v[74:75]
	v_mad_i32_i24 v43, v37, s63, v43
	v_mad_u64_u32 v[36:37], s[6:7], v70, s63, v[74:75]
	v_mad_u64_u32 v[40:41], s[6:7], v38, s63, v[74:75]
	v_mad_i32_i24 v41, v39, s63, v41
	v_mad_u64_u32 v[38:39], s[6:7], v72, s63, v[74:75]
	v_mad_i32_i24 v39, v73, s63, v39
	v_mad_i32_i24 v37, v71, s63, v37
	s_waitcnt vmcnt(1)
	v_lshlrev_b32_e32 v63, 16, v1
	s_waitcnt vmcnt(0)
	v_lshlrev_b32_e32 v13, 16, v5
	v_lshlrev_b32_e32 v17, 16, v4
	v_mul_f32_e32 v9, 0xbfb8aa3b, v17
	v_and_b32_e32 v21, 0xffff0000, v5
	v_mul_f32_e32 v5, 0xbfb8aa3b, v13
	v_exp_f32_e32 v60, v9
	v_exp_f32_e32 v61, v5
	ds_read_b128 v[56:59], v8
	ds_read_b128 v[8:11], v8 offset:16
	v_and_b32_e32 v25, 0xffff0000, v4
	v_mul_f32_e32 v4, 0xbfb8aa3b, v25
	v_pk_add_f32 v[60:61], v[60:61], 1.0 op_sel_hi:[1,0]
	s_waitcnt lgkmcnt(1)
; __device__ __forceinline__ unsigned pack2(float a, float b) { return (unsigned)f2bf(a) | ((unsigned)f2bf(b) << 16); }
; __device__ __forceinline__ float bflo(unsigned w) { return __uint_as_float(w << 16); }
; __device__ __forceinline__ float bfhi(unsigned w) { return __uint_as_float(w & 0xffff0000u); }
; __device__ __forceinline__ float silu_f(float g) { return g / (1.f + __expf(-g)); }
; __device__ void gmlp_item(const Params& p, int layer, int b, int n, int g, char* smem) {
;     ...
; #pragma unroll
;     for (int i = 0; i < 8; ++i) {
;       int q = tid + 256 * i, t = q >> 4, c = (q & 15) * 8;
;       float4 m0 = *reinterpret_cast<const float4*>(Tf + t * 132 + c);
;       float4 m1 = *reinterpret_cast<const float4*>(Tf + t * 132 + c + 4);
;       float mm[8] = {m0.x, m0.y, m0.z, m0.w, m1.x, m1.y, m1.z, m1.w};
;       unsigned uw[4] = {uu[i].x, uu[i].y, uu[i].z, uu[i].w};
;       unsigned gw[4] = {gt[i].x, gt[i].y, gt[i].z, gt[i].w};
;       unsigned ow[4];
; #pragma unroll
;       for (int e = 0; e < 4; ++e) {
;         float y0 = bflo(uw[e]) * mm[2 * e] * silu_f(bflo(gw[e]));
;         float y1 = bfhi(uw[e]) * mm[2 * e + 1] * silu_f(bfhi(gw[e]));
;         ow[e] = pack2(y0, y1);
;       }
;       *reinterpret_cast<uint4*>(Y + (t0 + t) * YW + g * 128 + c) = make_uint4(ow[0], ow[1], ow[2], ow[3]);
	v_mov_b32_e32 v64, v56
	v_exp_f32_e32 v4, v4
	v_lshlrev_b32_e32 v62, 16, v0
	v_mov_b32_e32 v65, v58
	v_rcp_f32_e32 v61, v61
	s_nop 0
	v_mul_f32_e32 v61, v13, v61
	v_and_b32_e32 v1, 0xffff0000, v1
	v_mul_f32_e32 v5, 0xbfb8aa3b, v21
	v_exp_f32_e32 v5, v5
	v_rcp_f32_e32 v60, v60
	s_nop 0
	v_mul_f32_e32 v60, v17, v60
	v_and_b32_e32 v0, 0xffff0000, v0
	v_mov_b32_e32 v58, v57
	v_pk_add_f32 v[4:5], v[4:5], 1.0 op_sel_hi:[1,0]
	v_pk_mul_f32 v[0:1], v[58:59], v[0:1]
	v_pk_mul_f32 v[62:63], v[64:65], v[62:63]
	v_rcp_f32_e32 v5, v5
	s_nop 0
	v_mul_f32_e32 v5, v21, v5
	v_pk_mul_f32 v[60:61], v[60:61], v[62:63]
	v_rcp_f32_e32 v4, v4
	s_nop 0
	v_mul_f32_e32 v4, v25, v4
	v_pk_mul_f32 v[0:1], v[4:5], v[0:1]
	v_cvt_pk_bf16_f32 v1, 0, v1
	v_cvt_pk_bf16_f32 v0, 0, v0
	v_cvt_pk_bf16_f32 v5, 0, v60
	v_cvt_pk_bf16_f32 v4, 0, v61
	v_and_b32_e32 v1, 0xffff0000, v1
	v_and_b32_e32 v0, 0xffff0000, v0
	v_lshlrev_b32_e32 v13, 16, v7
	v_lshlrev_b32_e32 v17, 16, v6
	v_or_b32_sdwa v1, v1, v4 dst_sel:DWORD dst_unused:UNUSED_PAD src0_sel:DWORD src1_sel:WORD_1
	v_or_b32_sdwa v0, v0, v5 dst_sel:DWORD dst_unused:UNUSED_PAD src0_sel:DWORD src1_sel:WORD_1
	v_mul_f32_e32 v4, 0xbfb8aa3b, v17
	v_mul_f32_e32 v5, 0xbfb8aa3b, v13
	v_exp_f32_e32 v4, v4
	v_exp_f32_e32 v5, v5
	v_and_b32_e32 v25, 0xffff0000, v6
	v_mul_f32_e32 v6, 0xbfb8aa3b, v25
	v_and_b32_e32 v21, 0xffff0000, v7
	v_exp_f32_e32 v60, v6
	v_pk_add_f32 v[64:65], v[4:5], 1.0 op_sel_hi:[1,0]
	global_load_dwordx4 v[4:7], v[14:15], off
	global_load_dwordx4 v[56:59], v[14:15], off offset:2048
	s_waitcnt lgkmcnt(0)
	v_mov_b32_e32 v14, v8
	v_mov_b32_e32 v15, v10
	v_lshlrev_b32_e32 v63, 16, v3
	v_lshlrev_b32_e32 v62, 16, v2
	v_pk_mul_f32 v[14:15], v[14:15], v[62:63]
	v_rcp_f32_e32 v63, v65
	s_nop 0
	v_mul_f32_e32 v63, v13, v63
	v_mul_f32_e32 v10, 0xbfb8aa3b, v21
	v_exp_f32_e32 v61, v10
	v_rcp_f32_e32 v62, v64
	s_nop 0
	v_mul_f32_e32 v62, v17, v62
	v_mov_b32_e32 v10, v9
	v_and_b32_e32 v3, 0xffff0000, v3
	v_pk_add_f32 v[60:61], v[60:61], 1.0 op_sel_hi:[1,0]
	v_and_b32_e32 v2, 0xffff0000, v2
	v_pk_mul_f32 v[2:3], v[10:11], v[2:3]
	v_pk_mul_f32 v[14:15], v[62:63], v[14:15]
	v_rcp_f32_e32 v9, v61
	s_nop 0
	v_mul_f32_e32 v9, v21, v9
	v_rcp_f32_e32 v8, v60
	s_nop 0
	v_mul_f32_e32 v8, v25, v8
	v_pk_mul_f32 v[2:3], v[8:9], v[2:3]
	v_cvt_pk_bf16_f32 v3, 0, v3
	v_cvt_pk_bf16_f32 v8, 0, v15
	v_and_b32_e32 v3, 0xffff0000, v3
	v_or_b32_sdwa v3, v3, v8 dst_sel:DWORD dst_unused:UNUSED_PAD src0_sel:DWORD src1_sel:WORD_1
	v_cvt_pk_bf16_f32 v2, 0, v2
	v_cvt_pk_bf16_f32 v9, 0, v14
	v_and_b32_e32 v2, 0xffff0000, v2
	v_or_b32_sdwa v2, v2, v9 dst_sel:DWORD dst_unused:UNUSED_PAD src0_sel:DWORD src1_sel:WORD_1
	s_waitcnt vmcnt(0)
	v_lshlrev_b32_e32 v21, 16, v56
	v_mul_f32_e32 v8, 0xbfb8aa3b, v21
	v_and_b32_e32 v29, 0xffff0000, v56
	v_lshlrev_b32_e32 v17, 16, v57
	v_exp_f32_e32 v60, v8
	v_mul_f32_e32 v8, 0xbfb8aa3b, v29
	v_exp_f32_e32 v56, v8
	v_mul_f32_e32 v8, 0xbfb8aa3b, v17
	v_exp_f32_e32 v61, v8
	ds_read_b128 v[8:11], v12
	ds_read_b128 v[12:15], v12 offset:16
	v_and_b32_e32 v25, 0xffff0000, v57
	v_lshlrev_b32_e32 v63, 16, v5
	v_pk_add_f32 v[60:61], v[60:61], 1.0 op_sel_hi:[1,0]
	s_waitcnt lgkmcnt(1)
	v_mov_b32_e32 v64, v8
	v_mov_b32_e32 v65, v10
	v_lshlrev_b32_e32 v62, 16, v4
	v_and_b32_e32 v5, 0xffff0000, v5
	v_rcp_f32_e32 v61, v61
	s_nop 0
	v_mul_f32_e32 v61, v17, v61
	v_and_b32_e32 v4, 0xffff0000, v4
	v_mul_f32_e32 v10, 0xbfb8aa3b, v25
	v_exp_f32_e32 v57, v10
	v_rcp_f32_e32 v60, v60
	s_nop 0
	v_mul_f32_e32 v60, v21, v60
	v_mov_b32_e32 v10, v9
	v_pk_mul_f32 v[4:5], v[10:11], v[4:5]
	v_pk_add_f32 v[56:57], v[56:57], 1.0 op_sel_hi:[1,0]
	v_pk_mul_f32 v[62:63], v[64:65], v[62:63]
	v_pk_mul_f32 v[60:61], v[60:61], v[62:63]
	v_lshlrev_b32_e32 v63, 16, v7
	v_lshlrev_b32_e32 v62, 16, v6
	v_rcp_f32_e32 v9, v57
	s_nop 0
	v_mul_f32_e32 v9, v25, v9
	v_rcp_f32_e32 v8, v56
	s_nop 0
	v_mul_f32_e32 v8, v29, v8
	v_pk_mul_f32 v[4:5], v[8:9], v[4:5]
	v_cvt_pk_bf16_f32 v5, 0, v5
	v_cvt_pk_bf16_f32 v4, 0, v4
	v_cvt_pk_bf16_f32 v9, 0, v60
	v_cvt_pk_bf16_f32 v8, 0, v61
	v_and_b32_e32 v5, 0xffff0000, v5
	v_and_b32_e32 v4, 0xffff0000, v4
	v_lshlrev_b32_e32 v17, 16, v59
	v_lshlrev_b32_e32 v21, 16, v58
	v_or_b32_sdwa v5, v5, v8 dst_sel:DWORD dst_unused:UNUSED_PAD src0_sel:DWORD src1_sel:WORD_1
	v_or_b32_sdwa v4, v4, v9 dst_sel:DWORD dst_unused:UNUSED_PAD src0_sel:DWORD src1_sel:WORD_1
	v_mul_f32_e32 v8, 0xbfb8aa3b, v21
	v_mul_f32_e32 v9, 0xbfb8aa3b, v17
	v_exp_f32_e32 v8, v8
	v_exp_f32_e32 v9, v9
	v_and_b32_e32 v29, 0xffff0000, v58
	v_mul_f32_e32 v10, 0xbfb8aa3b, v29
	v_and_b32_e32 v25, 0xffff0000, v59
	v_exp_f32_e32 v60, v10
	v_pk_add_f32 v[64:65], v[8:9], 1.0 op_sel_hi:[1,0]
	global_load_dwordx4 v[8:11], v[18:19], off
	global_load_dwordx4 v[56:59], v[18:19], off offset:2048
	s_waitcnt lgkmcnt(0)
	v_mov_b32_e32 v18, v12
	v_mov_b32_e32 v19, v14
	v_pk_mul_f32 v[18:19], v[18:19], v[62:63]
	v_rcp_f32_e32 v63, v65
	s_nop 0
	v_mul_f32_e32 v63, v17, v63
	v_and_b32_e32 v7, 0xffff0000, v7
	v_mul_f32_e32 v14, 0xbfb8aa3b, v25
	v_exp_f32_e32 v61, v14
	v_rcp_f32_e32 v62, v64
	s_nop 0
	v_mul_f32_e32 v62, v21, v62
	v_mov_b32_e32 v14, v13
	v_and_b32_e32 v6, 0xffff0000, v6
	v_pk_add_f32 v[60:61], v[60:61], 1.0 op_sel_hi:[1,0]
	v_pk_mul_f32 v[6:7], v[14:15], v[6:7]
	v_pk_mul_f32 v[18:19], v[62:63], v[18:19]
	v_rcp_f32_e32 v13, v61
	s_nop 0
	v_mul_f32_e32 v13, v25, v13
	v_rcp_f32_e32 v12, v60
	s_nop 0
	v_mul_f32_e32 v12, v29, v12
	v_pk_mul_f32 v[6:7], v[12:13], v[6:7]
	v_cvt_pk_bf16_f32 v7, 0, v7
	v_cvt_pk_bf16_f32 v12, 0, v19
	v_and_b32_e32 v7, 0xffff0000, v7
	v_or_b32_sdwa v7, v7, v12 dst_sel:DWORD dst_unused:UNUSED_PAD src0_sel:DWORD src1_sel:WORD_1
	v_cvt_pk_bf16_f32 v6, 0, v6
	v_cvt_pk_bf16_f32 v13, 0, v18
	v_and_b32_e32 v6, 0xffff0000, v6
	v_or_b32_sdwa v6, v6, v13 dst_sel:DWORD dst_unused:UNUSED_PAD src0_sel:DWORD src1_sel:WORD_1
	s_waitcnt vmcnt(1)
; __device__ __forceinline__ unsigned pack2(float a, float b) { return (unsigned)f2bf(a) | ((unsigned)f2bf(b) << 16); }
; __device__ __forceinline__ float bflo(unsigned w) { return __uint_as_float(w << 16); }
; __device__ __forceinline__ float bfhi(unsigned w) { return __uint_as_float(w & 0xffff0000u); }
; __device__ __forceinline__ float silu_f(float g) { return g / (1.f + __expf(-g)); }
; __device__ void gmlp_item(const Params& p, int layer, int b, int n, int g, char* smem) {
;     ...
; #pragma unroll
;     for (int i = 0; i < 8; ++i) {
;       int q = tid + 256 * i, t = q >> 4, c = (q & 15) * 8;
;       float4 m0 = *reinterpret_cast<const float4*>(Tf + t * 132 + c);
;       float4 m1 = *reinterpret_cast<const float4*>(Tf + t * 132 + c + 4);
;       float mm[8] = {m0.x, m0.y, m0.z, m0.w, m1.x, m1.y, m1.z, m1.w};
;       unsigned uw[4] = {uu[i].x, uu[i].y, uu[i].z, uu[i].w};
;       unsigned gw[4] = {gt[i].x, gt[i].y, gt[i].z, gt[i].w};
;       unsigned ow[4];
; #pragma unroll
;       for (int e = 0; e < 4; ++e) {
;         float y0 = bflo(uw[e]) * mm[2 * e] * silu_f(bflo(gw[e]));
;         float y1 = bfhi(uw[e]) * mm[2 * e + 1] * silu_f(bfhi(gw[e]));
;         ow[e] = pack2(y0, y1);
;       }
;       *reinterpret_cast<uint4*>(Y + (t0 + t) * YW + g * 128 + c) = make_uint4(ow[0], ow[1], ow[2], ow[3]);
	v_lshlrev_b32_e32 v63, 16, v9
	s_waitcnt vmcnt(0)
	v_lshlrev_b32_e32 v25, 16, v56
	v_mul_f32_e32 v12, 0xbfb8aa3b, v25
	v_and_b32_e32 v35, 0xffff0000, v56
	v_lshlrev_b32_e32 v21, 16, v57
	v_exp_f32_e32 v60, v12
	v_mul_f32_e32 v12, 0xbfb8aa3b, v35
	v_exp_f32_e32 v56, v12
	v_mul_f32_e32 v12, 0xbfb8aa3b, v21
	v_exp_f32_e32 v61, v12
	v_and_b32_e32 v29, 0xffff0000, v57
	ds_read_b128 v[12:15], v16
	ds_read_b128 v[16:19], v16 offset:16
	v_lshlrev_b32_e32 v62, 16, v8
	v_pk_add_f32 v[60:61], v[60:61], 1.0 op_sel_hi:[1,0]
	v_and_b32_e32 v9, 0xffff0000, v9
	s_waitcnt lgkmcnt(1)
	v_mov_b32_e32 v64, v12
	v_mov_b32_e32 v65, v14
	v_pk_mul_f32 v[62:63], v[64:65], v[62:63]
	v_rcp_f32_e32 v61, v61
	s_nop 0
	v_mul_f32_e32 v61, v21, v61
	v_and_b32_e32 v8, 0xffff0000, v8
	v_mul_f32_e32 v14, 0xbfb8aa3b, v29
	v_exp_f32_e32 v57, v14
	v_rcp_f32_e32 v60, v60
	s_nop 0
	v_mul_f32_e32 v60, v25, v60
	v_mov_b32_e32 v14, v13
	v_pk_mul_f32 v[8:9], v[14:15], v[8:9]
	v_pk_add_f32 v[56:57], v[56:57], 1.0 op_sel_hi:[1,0]
	v_pk_mul_f32 v[60:61], v[60:61], v[62:63]
	v_lshlrev_b32_e32 v63, 16, v11
	v_lshlrev_b32_e32 v62, 16, v10
	v_and_b32_e32 v11, 0xffff0000, v11
	v_rcp_f32_e32 v13, v57
	s_nop 0
	v_mul_f32_e32 v13, v29, v13
	v_rcp_f32_e32 v12, v56
	s_nop 0
	v_mul_f32_e32 v12, v35, v12
	v_pk_mul_f32 v[8:9], v[12:13], v[8:9]
	v_cvt_pk_bf16_f32 v9, 0, v9
	v_cvt_pk_bf16_f32 v8, 0, v8
	v_cvt_pk_bf16_f32 v13, 0, v60
	v_cvt_pk_bf16_f32 v12, 0, v61
	v_and_b32_e32 v9, 0xffff0000, v9
	v_and_b32_e32 v8, 0xffff0000, v8
	v_lshlrev_b32_e32 v21, 16, v59
	v_lshlrev_b32_e32 v25, 16, v58
	v_or_b32_sdwa v9, v9, v12 dst_sel:DWORD dst_unused:UNUSED_PAD src0_sel:DWORD src1_sel:WORD_1
	v_or_b32_sdwa v8, v8, v13 dst_sel:DWORD dst_unused:UNUSED_PAD src0_sel:DWORD src1_sel:WORD_1
	v_mul_f32_e32 v12, 0xbfb8aa3b, v25
	v_mul_f32_e32 v13, 0xbfb8aa3b, v21
	v_exp_f32_e32 v12, v12
	v_exp_f32_e32 v13, v13
	v_and_b32_e32 v35, 0xffff0000, v58
	v_mul_f32_e32 v14, 0xbfb8aa3b, v35
	v_and_b32_e32 v29, 0xffff0000, v59
	v_exp_f32_e32 v60, v14
	v_pk_add_f32 v[64:65], v[12:13], 1.0 op_sel_hi:[1,0]
	global_load_dwordx4 v[12:15], v[22:23], off
	global_load_dwordx4 v[56:59], v[22:23], off offset:2048
	s_waitcnt lgkmcnt(0)
	v_mov_b32_e32 v22, v16
	v_mov_b32_e32 v23, v18
	v_pk_mul_f32 v[22:23], v[22:23], v[62:63]
	v_rcp_f32_e32 v63, v65
	s_nop 0
	v_mul_f32_e32 v63, v21, v63
	v_and_b32_e32 v10, 0xffff0000, v10
	v_mul_f32_e32 v18, 0xbfb8aa3b, v29
	v_exp_f32_e32 v61, v18
	v_rcp_f32_e32 v62, v64
	s_nop 0
	v_mul_f32_e32 v62, v25, v62
	v_mov_b32_e32 v18, v17
	v_pk_mul_f32 v[10:11], v[18:19], v[10:11]
	v_pk_add_f32 v[60:61], v[60:61], 1.0 op_sel_hi:[1,0]
	v_pk_mul_f32 v[22:23], v[62:63], v[22:23]
	s_waitcnt vmcnt(1)
	v_lshlrev_b32_e32 v63, 16, v13
	v_rcp_f32_e32 v17, v61
	s_nop 0
	v_mul_f32_e32 v17, v29, v17
	v_rcp_f32_e32 v16, v60
	s_nop 0
	v_mul_f32_e32 v16, v35, v16
	v_pk_mul_f32 v[10:11], v[16:17], v[10:11]
	v_cvt_pk_bf16_f32 v11, 0, v11
	v_cvt_pk_bf16_f32 v16, 0, v23
	v_and_b32_e32 v11, 0xffff0000, v11
	s_waitcnt vmcnt(0)
	v_lshlrev_b32_e32 v29, 16, v56
	v_or_b32_sdwa v11, v11, v16 dst_sel:DWORD dst_unused:UNUSED_PAD src0_sel:DWORD src1_sel:WORD_1
	v_mul_f32_e32 v16, 0xbfb8aa3b, v29
	v_and_b32_e32 v55, 0xffff0000, v56
	v_lshlrev_b32_e32 v25, 16, v57
	v_exp_f32_e32 v60, v16
	v_mul_f32_e32 v16, 0xbfb8aa3b, v55
	v_exp_f32_e32 v56, v16
	v_mul_f32_e32 v16, 0xbfb8aa3b, v25
	v_exp_f32_e32 v61, v16
	v_cvt_pk_bf16_f32 v10, 0, v10
	v_pk_add_f32 v[60:61], v[60:61], 1.0 op_sel_hi:[1,0]
	v_cvt_pk_bf16_f32 v17, 0, v22
	v_and_b32_e32 v10, 0xffff0000, v10
	v_and_b32_e32 v35, 0xffff0000, v57
	v_or_b32_sdwa v10, v10, v17 dst_sel:DWORD dst_unused:UNUSED_PAD src0_sel:DWORD src1_sel:WORD_1
	ds_read_b128 v[16:19], v20
	ds_read_b128 v[20:23], v20 offset:16
	v_lshlrev_b32_e32 v62, 16, v12
	v_and_b32_e32 v13, 0xffff0000, v13
	s_waitcnt lgkmcnt(1)
	v_mov_b32_e32 v64, v16
	v_mov_b32_e32 v65, v18
	v_pk_mul_f32 v[62:63], v[64:65], v[62:63]
	v_rcp_f32_e32 v61, v61
	s_nop 0
	v_mul_f32_e32 v61, v25, v61
	v_and_b32_e32 v12, 0xffff0000, v12
	v_mul_f32_e32 v18, 0xbfb8aa3b, v35
	v_exp_f32_e32 v57, v18
	v_rcp_f32_e32 v60, v60
	s_nop 0
	v_mul_f32_e32 v60, v29, v60
	v_mov_b32_e32 v18, v17
	v_pk_mul_f32 v[12:13], v[18:19], v[12:13]
	v_pk_add_f32 v[56:57], v[56:57], 1.0 op_sel_hi:[1,0]
	v_pk_mul_f32 v[60:61], v[60:61], v[62:63]
	v_lshlrev_b32_e32 v63, 16, v15
	v_lshlrev_b32_e32 v62, 16, v14
	v_and_b32_e32 v15, 0xffff0000, v15
	v_rcp_f32_e32 v17, v57
	s_nop 0
	v_mul_f32_e32 v17, v35, v17
	v_rcp_f32_e32 v16, v56
	s_nop 0
	v_mul_f32_e32 v16, v55, v16
	v_pk_mul_f32 v[12:13], v[16:17], v[12:13]
	v_cvt_pk_bf16_f32 v13, 0, v13
	v_cvt_pk_bf16_f32 v12, 0, v12
	v_cvt_pk_bf16_f32 v17, 0, v60
	v_cvt_pk_bf16_f32 v16, 0, v61
	v_and_b32_e32 v13, 0xffff0000, v13
	v_and_b32_e32 v12, 0xffff0000, v12
	v_lshlrev_b32_e32 v25, 16, v59
	v_lshlrev_b32_e32 v29, 16, v58
	v_or_b32_sdwa v13, v13, v16 dst_sel:DWORD dst_unused:UNUSED_PAD src0_sel:DWORD src1_sel:WORD_1
	v_or_b32_sdwa v12, v12, v17 dst_sel:DWORD dst_unused:UNUSED_PAD src0_sel:DWORD src1_sel:WORD_1
	v_mul_f32_e32 v16, 0xbfb8aa3b, v29
	v_mul_f32_e32 v17, 0xbfb8aa3b, v25
	v_exp_f32_e32 v16, v16
	v_exp_f32_e32 v17, v17
	v_and_b32_e32 v55, 0xffff0000, v58
	v_mul_f32_e32 v18, 0xbfb8aa3b, v55
	v_and_b32_e32 v35, 0xffff0000, v59
	v_exp_f32_e32 v60, v18
	v_pk_add_f32 v[64:65], v[16:17], 1.0 op_sel_hi:[1,0]
	global_load_dwordx4 v[16:19], v[26:27], off
	global_load_dwordx4 v[56:59], v[26:27], off offset:2048
	s_waitcnt lgkmcnt(0)
; __device__ __forceinline__ unsigned pack2(float a, float b) { return (unsigned)f2bf(a) | ((unsigned)f2bf(b) << 16); }
; __device__ __forceinline__ float bflo(unsigned w) { return __uint_as_float(w << 16); }
; __device__ __forceinline__ float bfhi(unsigned w) { return __uint_as_float(w & 0xffff0000u); }
; __device__ __forceinline__ float silu_f(float g) { return g / (1.f + __expf(-g)); }
; __device__ void gmlp_item(const Params& p, int layer, int b, int n, int g, char* smem) {
;     ...
; #pragma unroll
;     for (int i = 0; i < 8; ++i) {
;       int q = tid + 256 * i, t = q >> 4, c = (q & 15) * 8;
;       float4 m0 = *reinterpret_cast<const float4*>(Tf + t * 132 + c);
;       float4 m1 = *reinterpret_cast<const float4*>(Tf + t * 132 + c + 4);
;       float mm[8] = {m0.x, m0.y, m0.z, m0.w, m1.x, m1.y, m1.z, m1.w};
;       unsigned uw[4] = {uu[i].x, uu[i].y, uu[i].z, uu[i].w};
;       unsigned gw[4] = {gt[i].x, gt[i].y, gt[i].z, gt[i].w};
;       unsigned ow[4];
; #pragma unroll
;       for (int e = 0; e < 4; ++e) {
;         float y0 = bflo(uw[e]) * mm[2 * e] * silu_f(bflo(gw[e]));
;         float y1 = bfhi(uw[e]) * mm[2 * e + 1] * silu_f(bfhi(gw[e]));
;         ow[e] = pack2(y0, y1);
;       }
;       *reinterpret_cast<uint4*>(Y + (t0 + t) * YW + g * 128 + c) = make_uint4(ow[0], ow[1], ow[2], ow[3]);
	v_mov_b32_e32 v26, v20
	v_mov_b32_e32 v27, v22
	v_pk_mul_f32 v[26:27], v[26:27], v[62:63]
	v_rcp_f32_e32 v63, v65
	s_nop 0
	v_mul_f32_e32 v63, v25, v63
	v_and_b32_e32 v14, 0xffff0000, v14
	v_mul_f32_e32 v22, 0xbfb8aa3b, v35
	v_exp_f32_e32 v61, v22
	v_rcp_f32_e32 v62, v64
	s_nop 0
	v_mul_f32_e32 v62, v29, v62
	v_mov_b32_e32 v22, v21
	v_pk_mul_f32 v[14:15], v[22:23], v[14:15]
	v_pk_add_f32 v[60:61], v[60:61], 1.0 op_sel_hi:[1,0]
	v_pk_mul_f32 v[26:27], v[62:63], v[26:27]
	s_waitcnt vmcnt(1)
	v_lshlrev_b32_e32 v63, 16, v17
	v_rcp_f32_e32 v21, v61
	s_nop 0
	v_mul_f32_e32 v21, v35, v21
	v_rcp_f32_e32 v20, v60
	s_nop 0
	v_mul_f32_e32 v20, v55, v20
	v_pk_mul_f32 v[14:15], v[20:21], v[14:15]
	v_cvt_pk_bf16_f32 v15, 0, v15
	v_cvt_pk_bf16_f32 v20, 0, v27
	v_and_b32_e32 v15, 0xffff0000, v15
	s_waitcnt vmcnt(0)
	v_lshlrev_b32_e32 v35, 16, v56
	v_or_b32_sdwa v15, v15, v20 dst_sel:DWORD dst_unused:UNUSED_PAD src0_sel:DWORD src1_sel:WORD_1
	v_mul_f32_e32 v20, 0xbfb8aa3b, v35
	v_and_b32_e32 v66, 0xffff0000, v56
	v_lshlrev_b32_e32 v29, 16, v57
	v_exp_f32_e32 v60, v20
	v_mul_f32_e32 v20, 0xbfb8aa3b, v66
	v_exp_f32_e32 v56, v20
	v_mul_f32_e32 v20, 0xbfb8aa3b, v29
	v_exp_f32_e32 v61, v20
	v_cvt_pk_bf16_f32 v14, 0, v14
	v_pk_add_f32 v[60:61], v[60:61], 1.0 op_sel_hi:[1,0]
	v_cvt_pk_bf16_f32 v21, 0, v26
	v_and_b32_e32 v14, 0xffff0000, v14
	v_and_b32_e32 v55, 0xffff0000, v57
	v_or_b32_sdwa v14, v14, v21 dst_sel:DWORD dst_unused:UNUSED_PAD src0_sel:DWORD src1_sel:WORD_1
	ds_read_b128 v[20:23], v24
	ds_read_b128 v[24:27], v24 offset:16
	v_lshlrev_b32_e32 v62, 16, v16
	v_and_b32_e32 v17, 0xffff0000, v17
	s_waitcnt lgkmcnt(1)
	v_mov_b32_e32 v64, v20
	v_mov_b32_e32 v65, v22
	v_pk_mul_f32 v[62:63], v[64:65], v[62:63]
	v_rcp_f32_e32 v61, v61
	s_nop 0
	v_mul_f32_e32 v61, v29, v61
	v_and_b32_e32 v16, 0xffff0000, v16
	v_mul_f32_e32 v22, 0xbfb8aa3b, v55
	v_exp_f32_e32 v57, v22
	v_rcp_f32_e32 v60, v60
	s_nop 0
	v_mul_f32_e32 v60, v35, v60
	v_mov_b32_e32 v22, v21
	v_pk_mul_f32 v[16:17], v[22:23], v[16:17]
	v_pk_add_f32 v[56:57], v[56:57], 1.0 op_sel_hi:[1,0]
	v_pk_mul_f32 v[60:61], v[60:61], v[62:63]
	v_lshlrev_b32_e32 v63, 16, v19
	v_lshlrev_b32_e32 v62, 16, v18
	v_and_b32_e32 v19, 0xffff0000, v19
	v_rcp_f32_e32 v21, v57
	s_nop 0
	v_mul_f32_e32 v21, v55, v21
	v_rcp_f32_e32 v20, v56
	s_nop 0
	v_mul_f32_e32 v20, v66, v20
	v_pk_mul_f32 v[16:17], v[20:21], v[16:17]
	v_cvt_pk_bf16_f32 v17, 0, v17
	v_cvt_pk_bf16_f32 v16, 0, v16
	v_cvt_pk_bf16_f32 v21, 0, v60
	v_cvt_pk_bf16_f32 v20, 0, v61
	v_and_b32_e32 v17, 0xffff0000, v17
	v_and_b32_e32 v16, 0xffff0000, v16
	v_lshlrev_b32_e32 v29, 16, v59
	v_lshlrev_b32_e32 v35, 16, v58
	v_or_b32_sdwa v17, v17, v20 dst_sel:DWORD dst_unused:UNUSED_PAD src0_sel:DWORD src1_sel:WORD_1
	v_or_b32_sdwa v16, v16, v21 dst_sel:DWORD dst_unused:UNUSED_PAD src0_sel:DWORD src1_sel:WORD_1
	v_mul_f32_e32 v20, 0xbfb8aa3b, v35
	v_mul_f32_e32 v21, 0xbfb8aa3b, v29
	v_exp_f32_e32 v20, v20
	v_exp_f32_e32 v21, v21
	v_and_b32_e32 v66, 0xffff0000, v58
	v_mul_f32_e32 v22, 0xbfb8aa3b, v66
	v_and_b32_e32 v55, 0xffff0000, v59
	v_exp_f32_e32 v60, v22
	v_pk_add_f32 v[64:65], v[20:21], 1.0 op_sel_hi:[1,0]
	global_load_dwordx4 v[20:23], v[30:31], off
	global_load_dwordx4 v[56:59], v[30:31], off offset:2048
	s_waitcnt lgkmcnt(0)
	v_mov_b32_e32 v30, v24
	v_mov_b32_e32 v31, v26
	v_pk_mul_f32 v[30:31], v[30:31], v[62:63]
	v_rcp_f32_e32 v63, v65
	s_nop 0
	v_mul_f32_e32 v63, v29, v63
	v_and_b32_e32 v18, 0xffff0000, v18
	v_mul_f32_e32 v26, 0xbfb8aa3b, v55
	v_exp_f32_e32 v61, v26
	v_rcp_f32_e32 v62, v64
	s_nop 0
	v_mul_f32_e32 v62, v35, v62
	v_mov_b32_e32 v26, v25
	v_pk_mul_f32 v[18:19], v[26:27], v[18:19]
	v_pk_add_f32 v[60:61], v[60:61], 1.0 op_sel_hi:[1,0]
	v_pk_mul_f32 v[30:31], v[62:63], v[30:31]
	s_waitcnt vmcnt(1)
	v_lshlrev_b32_e32 v63, 16, v21
	v_rcp_f32_e32 v25, v61
	s_nop 0
	v_mul_f32_e32 v25, v55, v25
	v_rcp_f32_e32 v24, v60
	s_nop 0
	v_mul_f32_e32 v24, v66, v24
	v_pk_mul_f32 v[18:19], v[24:25], v[18:19]
	v_cvt_pk_bf16_f32 v19, 0, v19
	v_cvt_pk_bf16_f32 v24, 0, v31
	v_and_b32_e32 v19, 0xffff0000, v19
	s_waitcnt vmcnt(0)
	v_lshlrev_b32_e32 v55, 16, v56
	v_or_b32_sdwa v19, v19, v24 dst_sel:DWORD dst_unused:UNUSED_PAD src0_sel:DWORD src1_sel:WORD_1
	v_mul_f32_e32 v24, 0xbfb8aa3b, v55
	v_and_b32_e32 v67, 0xffff0000, v56
	v_lshlrev_b32_e32 v35, 16, v57
	v_exp_f32_e32 v60, v24
	v_mul_f32_e32 v24, 0xbfb8aa3b, v67
	v_exp_f32_e32 v56, v24
	v_mul_f32_e32 v24, 0xbfb8aa3b, v35
	v_exp_f32_e32 v61, v24
	v_cvt_pk_bf16_f32 v18, 0, v18
	v_pk_add_f32 v[60:61], v[60:61], 1.0 op_sel_hi:[1,0]
	v_cvt_pk_bf16_f32 v25, 0, v30
	v_and_b32_e32 v18, 0xffff0000, v18
	v_and_b32_e32 v66, 0xffff0000, v57
	v_or_b32_sdwa v18, v18, v25 dst_sel:DWORD dst_unused:UNUSED_PAD src0_sel:DWORD src1_sel:WORD_1
	ds_read_b128 v[24:27], v28
	ds_read_b128 v[28:31], v28 offset:16
	v_lshlrev_b32_e32 v62, 16, v20
	v_and_b32_e32 v21, 0xffff0000, v21
	s_waitcnt lgkmcnt(1)
; __device__ __forceinline__ unsigned pack2(float a, float b) { return (unsigned)f2bf(a) | ((unsigned)f2bf(b) << 16); }
; __device__ __forceinline__ float bflo(unsigned w) { return __uint_as_float(w << 16); }
; __device__ __forceinline__ float bfhi(unsigned w) { return __uint_as_float(w & 0xffff0000u); }
; __device__ __forceinline__ float silu_f(float g) { return g / (1.f + __expf(-g)); }
; __device__ void gmlp_item(const Params& p, int layer, int b, int n, int g, char* smem) {
;     ...
; #pragma unroll
;     for (int i = 0; i < 8; ++i) {
;       int q = tid + 256 * i, t = q >> 4, c = (q & 15) * 8;
;       float4 m0 = *reinterpret_cast<const float4*>(Tf + t * 132 + c);
;       float4 m1 = *reinterpret_cast<const float4*>(Tf + t * 132 + c + 4);
;       float mm[8] = {m0.x, m0.y, m0.z, m0.w, m1.x, m1.y, m1.z, m1.w};
;       unsigned uw[4] = {uu[i].x, uu[i].y, uu[i].z, uu[i].w};
;       unsigned gw[4] = {gt[i].x, gt[i].y, gt[i].z, gt[i].w};
;       unsigned ow[4];
; #pragma unroll
;       for (int e = 0; e < 4; ++e) {
;         float y0 = bflo(uw[e]) * mm[2 * e] * silu_f(bflo(gw[e]));
;         float y1 = bfhi(uw[e]) * mm[2 * e + 1] * silu_f(bfhi(gw[e]));
;         ow[e] = pack2(y0, y1);
;       }
;       *reinterpret_cast<uint4*>(Y + (t0 + t) * YW + g * 128 + c) = make_uint4(ow[0], ow[1], ow[2], ow[3]);
	v_mov_b32_e32 v64, v24
	v_mov_b32_e32 v65, v26
	v_pk_mul_f32 v[62:63], v[64:65], v[62:63]
	v_rcp_f32_e32 v61, v61
	s_nop 0
	v_mul_f32_e32 v61, v35, v61
	v_and_b32_e32 v20, 0xffff0000, v20
	v_mul_f32_e32 v26, 0xbfb8aa3b, v66
	v_exp_f32_e32 v57, v26
	v_rcp_f32_e32 v60, v60
	s_nop 0
	v_mul_f32_e32 v60, v55, v60
	v_mov_b32_e32 v26, v25
	v_pk_mul_f32 v[20:21], v[26:27], v[20:21]
	v_pk_add_f32 v[56:57], v[56:57], 1.0 op_sel_hi:[1,0]
	v_pk_mul_f32 v[60:61], v[60:61], v[62:63]
	v_lshlrev_b32_e32 v63, 16, v23
	v_lshlrev_b32_e32 v62, 16, v22
	v_and_b32_e32 v23, 0xffff0000, v23
	v_rcp_f32_e32 v25, v57
	s_nop 0
	v_mul_f32_e32 v25, v66, v25
	v_rcp_f32_e32 v24, v56
	s_nop 0
	v_mul_f32_e32 v24, v67, v24
	v_pk_mul_f32 v[20:21], v[24:25], v[20:21]
	v_cvt_pk_bf16_f32 v21, 0, v21
	v_cvt_pk_bf16_f32 v20, 0, v20
	v_cvt_pk_bf16_f32 v25, 0, v60
	v_cvt_pk_bf16_f32 v24, 0, v61
	v_and_b32_e32 v21, 0xffff0000, v21
	v_and_b32_e32 v20, 0xffff0000, v20
	v_lshlrev_b32_e32 v35, 16, v59
	v_lshlrev_b32_e32 v55, 16, v58
	v_or_b32_sdwa v21, v21, v24 dst_sel:DWORD dst_unused:UNUSED_PAD src0_sel:DWORD src1_sel:WORD_1
	v_or_b32_sdwa v20, v20, v25 dst_sel:DWORD dst_unused:UNUSED_PAD src0_sel:DWORD src1_sel:WORD_1
	v_mul_f32_e32 v24, 0xbfb8aa3b, v55
	v_mul_f32_e32 v25, 0xbfb8aa3b, v35
	v_exp_f32_e32 v24, v24
	v_exp_f32_e32 v25, v25
	v_and_b32_e32 v67, 0xffff0000, v58
	v_mul_f32_e32 v26, 0xbfb8aa3b, v67
	v_and_b32_e32 v66, 0xffff0000, v59
	v_exp_f32_e32 v60, v26
	v_pk_add_f32 v[64:65], v[24:25], 1.0 op_sel_hi:[1,0]
	global_load_dwordx4 v[24:27], v[32:33], off
	global_load_dwordx4 v[56:59], v[32:33], off offset:2048
	s_waitcnt lgkmcnt(0)
	v_mov_b32_e32 v32, v28
	v_mov_b32_e32 v33, v30
	v_pk_mul_f32 v[32:33], v[32:33], v[62:63]
	v_rcp_f32_e32 v63, v65
	s_nop 0
	v_mul_f32_e32 v63, v35, v63
	v_and_b32_e32 v22, 0xffff0000, v22
	v_mul_f32_e32 v30, 0xbfb8aa3b, v66
	v_exp_f32_e32 v61, v30
	v_rcp_f32_e32 v62, v64
	s_nop 0
	v_mul_f32_e32 v62, v55, v62
	v_mov_b32_e32 v30, v29
	v_pk_mul_f32 v[22:23], v[30:31], v[22:23]
	v_pk_add_f32 v[60:61], v[60:61], 1.0 op_sel_hi:[1,0]
	v_pk_mul_f32 v[32:33], v[62:63], v[32:33]
	s_waitcnt vmcnt(1)
	v_lshlrev_b32_e32 v63, 16, v25
	v_rcp_f32_e32 v29, v61
	s_nop 0
	v_mul_f32_e32 v29, v66, v29
	v_rcp_f32_e32 v28, v60
	s_nop 0
	v_mul_f32_e32 v28, v67, v28
	v_pk_mul_f32 v[22:23], v[28:29], v[22:23]
	v_cvt_pk_bf16_f32 v23, 0, v23
	v_cvt_pk_bf16_f32 v28, 0, v33
	v_and_b32_e32 v23, 0xffff0000, v23
	s_waitcnt vmcnt(0)
	v_lshlrev_b32_e32 v66, 16, v56
	v_or_b32_sdwa v23, v23, v28 dst_sel:DWORD dst_unused:UNUSED_PAD src0_sel:DWORD src1_sel:WORD_1
	v_mul_f32_e32 v28, 0xbfb8aa3b, v66
	v_and_b32_e32 v68, 0xffff0000, v56
	v_lshlrev_b32_e32 v55, 16, v57
	v_exp_f32_e32 v60, v28
	v_mul_f32_e32 v28, 0xbfb8aa3b, v68
	v_exp_f32_e32 v56, v28
	v_mul_f32_e32 v28, 0xbfb8aa3b, v55
	v_exp_f32_e32 v61, v28
	v_cvt_pk_bf16_f32 v22, 0, v22
	v_pk_add_f32 v[60:61], v[60:61], 1.0 op_sel_hi:[1,0]
	v_cvt_pk_bf16_f32 v29, 0, v32
	v_and_b32_e32 v22, 0xffff0000, v22
	v_and_b32_e32 v67, 0xffff0000, v57
	v_or_b32_sdwa v22, v22, v29 dst_sel:DWORD dst_unused:UNUSED_PAD src0_sel:DWORD src1_sel:WORD_1
	ds_read_b128 v[28:31], v34
	ds_read_b128 v[32:35], v34 offset:16
	v_lshlrev_b32_e32 v62, 16, v24
	v_and_b32_e32 v25, 0xffff0000, v25
	s_waitcnt lgkmcnt(1)
	v_mov_b32_e32 v64, v28
	v_mov_b32_e32 v65, v30
	v_pk_mul_f32 v[62:63], v[64:65], v[62:63]
	v_rcp_f32_e32 v61, v61
	s_nop 0
	v_mul_f32_e32 v61, v55, v61
	v_and_b32_e32 v24, 0xffff0000, v24
	v_mul_f32_e32 v30, 0xbfb8aa3b, v67
	v_exp_f32_e32 v57, v30
	v_rcp_f32_e32 v60, v60
	s_nop 0
	v_mul_f32_e32 v60, v66, v60
	v_mov_b32_e32 v30, v29
	v_pk_mul_f32 v[24:25], v[30:31], v[24:25]
	v_pk_add_f32 v[56:57], v[56:57], 1.0 op_sel_hi:[1,0]
	v_pk_mul_f32 v[60:61], v[60:61], v[62:63]
	v_lshlrev_b32_e32 v66, 16, v58
	v_lshlrev_b32_e32 v63, 16, v27
	v_and_b32_e32 v27, 0xffff0000, v27
	v_rcp_f32_e32 v29, v57
	s_nop 0
	v_mul_f32_e32 v29, v67, v29
	v_rcp_f32_e32 v28, v56
	s_nop 0
	v_mul_f32_e32 v28, v68, v28
	v_pk_mul_f32 v[24:25], v[28:29], v[24:25]
	v_cvt_pk_bf16_f32 v25, 0, v25
	v_cvt_pk_bf16_f32 v24, 0, v24
	v_cvt_pk_bf16_f32 v29, 0, v60
	v_cvt_pk_bf16_f32 v28, 0, v61
	v_and_b32_e32 v25, 0xffff0000, v25
	v_and_b32_e32 v24, 0xffff0000, v24
	v_lshlrev_b32_e32 v55, 16, v59
	v_or_b32_sdwa v25, v25, v28 dst_sel:DWORD dst_unused:UNUSED_PAD src0_sel:DWORD src1_sel:WORD_1
	v_or_b32_sdwa v24, v24, v29 dst_sel:DWORD dst_unused:UNUSED_PAD src0_sel:DWORD src1_sel:WORD_1
	v_mul_f32_e32 v28, 0xbfb8aa3b, v66
	v_mul_f32_e32 v29, 0xbfb8aa3b, v55
	v_exp_f32_e32 v28, v28
	v_exp_f32_e32 v29, v29
	v_and_b32_e32 v68, 0xffff0000, v58
	v_mul_f32_e32 v30, 0xbfb8aa3b, v68
	v_and_b32_e32 v67, 0xffff0000, v59
	v_exp_f32_e32 v60, v30
	v_pk_add_f32 v[64:65], v[28:29], 1.0 op_sel_hi:[1,0]
	global_load_dwordx4 v[28:31], v[52:53], off
	global_load_dwordx4 v[56:59], v[52:53], off offset:2048
	s_waitcnt lgkmcnt(0)
; __device__ __forceinline__ unsigned pack2(float a, float b) { return (unsigned)f2bf(a) | ((unsigned)f2bf(b) << 16); }
; __device__ __forceinline__ float bflo(unsigned w) { return __uint_as_float(w << 16); }
; __device__ __forceinline__ float bfhi(unsigned w) { return __uint_as_float(w & 0xffff0000u); }
; __device__ __forceinline__ float silu_f(float g) { return g / (1.f + __expf(-g)); }
; __device__ void gmlp_item(const Params& p, int layer, int b, int n, int g, char* smem) {
;     ...
; #pragma unroll
;     for (int i = 0; i < 8; ++i) {
;       int q = tid + 256 * i, t = q >> 4, c = (q & 15) * 8;
;       float4 m0 = *reinterpret_cast<const float4*>(Tf + t * 132 + c);
;       float4 m1 = *reinterpret_cast<const float4*>(Tf + t * 132 + c + 4);
;       float mm[8] = {m0.x, m0.y, m0.z, m0.w, m1.x, m1.y, m1.z, m1.w};
;       unsigned uw[4] = {uu[i].x, uu[i].y, uu[i].z, uu[i].w};
;       unsigned gw[4] = {gt[i].x, gt[i].y, gt[i].z, gt[i].w};
;       unsigned ow[4];
; #pragma unroll
;       for (int e = 0; e < 4; ++e) {
;         float y0 = bflo(uw[e]) * mm[2 * e] * silu_f(bflo(gw[e]));
;         float y1 = bfhi(uw[e]) * mm[2 * e + 1] * silu_f(bfhi(gw[e]));
;         ow[e] = pack2(y0, y1);
;       }
;       *reinterpret_cast<uint4*>(Y + (t0 + t) * YW + g * 128 + c) = make_uint4(ow[0], ow[1], ow[2], ow[3]);
	v_mov_b32_e32 v52, v32
	v_lshlrev_b32_e32 v62, 16, v26
	v_mov_b32_e32 v53, v34
	v_pk_mul_f32 v[52:53], v[52:53], v[62:63]
	v_rcp_f32_e32 v63, v65
	s_nop 0
	v_mul_f32_e32 v63, v55, v63
	v_and_b32_e32 v26, 0xffff0000, v26
	v_mul_f32_e32 v34, 0xbfb8aa3b, v67
	v_exp_f32_e32 v61, v34
	v_rcp_f32_e32 v62, v64
	s_nop 0
	v_mul_f32_e32 v62, v66, v62
	v_mov_b32_e32 v34, v33
	v_pk_mul_f32 v[26:27], v[34:35], v[26:27]
	v_pk_add_f32 v[60:61], v[60:61], 1.0 op_sel_hi:[1,0]
	v_pk_mul_f32 v[52:53], v[62:63], v[52:53]
	s_waitcnt vmcnt(1)
	v_lshlrev_b32_e32 v63, 16, v29
	v_rcp_f32_e32 v33, v61
	s_nop 0
	v_mul_f32_e32 v33, v67, v33
	v_rcp_f32_e32 v32, v60
	s_nop 0
	v_mul_f32_e32 v32, v68, v32
	v_pk_mul_f32 v[26:27], v[32:33], v[26:27]
	v_cvt_pk_bf16_f32 v27, 0, v27
	v_cvt_pk_bf16_f32 v32, 0, v53
	v_and_b32_e32 v27, 0xffff0000, v27
	s_waitcnt vmcnt(0)
	v_lshlrev_b32_e32 v67, 16, v56
	v_or_b32_sdwa v27, v27, v32 dst_sel:DWORD dst_unused:UNUSED_PAD src0_sel:DWORD src1_sel:WORD_1
	v_mul_f32_e32 v32, 0xbfb8aa3b, v67
	v_and_b32_e32 v69, 0xffff0000, v56
	v_lshlrev_b32_e32 v66, 16, v57
	v_exp_f32_e32 v60, v32
	v_mul_f32_e32 v32, 0xbfb8aa3b, v69
	v_exp_f32_e32 v56, v32
	v_mul_f32_e32 v32, 0xbfb8aa3b, v66
	v_exp_f32_e32 v61, v32
	v_cvt_pk_bf16_f32 v26, 0, v26
	v_pk_add_f32 v[60:61], v[60:61], 1.0 op_sel_hi:[1,0]
	v_cvt_pk_bf16_f32 v33, 0, v52
	v_and_b32_e32 v26, 0xffff0000, v26
	v_and_b32_e32 v68, 0xffff0000, v57
	v_or_b32_sdwa v26, v26, v33 dst_sel:DWORD dst_unused:UNUSED_PAD src0_sel:DWORD src1_sel:WORD_1
	ds_read_b128 v[32:35], v54
	ds_read_b128 v[52:55], v54 offset:16
	v_lshlrev_b32_e32 v62, 16, v28
	v_and_b32_e32 v29, 0xffff0000, v29
	s_waitcnt lgkmcnt(1)
	v_mov_b32_e32 v64, v32
	v_mov_b32_e32 v65, v34
	v_pk_mul_f32 v[62:63], v[64:65], v[62:63]
	v_rcp_f32_e32 v61, v61
	s_nop 0
	v_mul_f32_e32 v61, v66, v61
	v_and_b32_e32 v28, 0xffff0000, v28
	v_mul_f32_e32 v34, 0xbfb8aa3b, v68
	v_exp_f32_e32 v57, v34
	v_rcp_f32_e32 v60, v60
	s_nop 0
	v_mul_f32_e32 v60, v67, v60
	v_pk_mul_f32 v[60:61], v[60:61], v[62:63]
	v_mov_b32_e32 v34, v33
	v_pk_add_f32 v[56:57], v[56:57], 1.0 op_sel_hi:[1,0]
	v_pk_mul_f32 v[28:29], v[34:35], v[28:29]
	s_nop 0
	v_rcp_f32_e32 v33, v57
	s_nop 0
	v_mul_f32_e32 v33, v68, v33
	v_rcp_f32_e32 v32, v56
	s_nop 0
	v_mul_f32_e32 v32, v69, v32
	v_pk_mul_f32 v[28:29], v[32:33], v[28:29]
	v_cvt_pk_bf16_f32 v29, 0, v29
	v_cvt_pk_bf16_f32 v28, 0, v28
	v_cvt_pk_bf16_f32 v33, 0, v60
	v_cvt_pk_bf16_f32 v32, 0, v61
	v_and_b32_e32 v29, 0xffff0000, v29
	v_and_b32_e32 v28, 0xffff0000, v28
	v_lshlrev_b32_e32 v35, 16, v59
	v_lshlrev_b32_e32 v60, 16, v58
	v_or_b32_sdwa v29, v29, v32 dst_sel:DWORD dst_unused:UNUSED_PAD src0_sel:DWORD src1_sel:WORD_1
	v_or_b32_sdwa v28, v28, v33 dst_sel:DWORD dst_unused:UNUSED_PAD src0_sel:DWORD src1_sel:WORD_1
	v_mul_f32_e32 v32, 0xbfb8aa3b, v60
	v_mul_f32_e32 v33, 0xbfb8aa3b, v35
	v_exp_f32_e32 v32, v32
	v_exp_f32_e32 v33, v33
	v_and_b32_e32 v62, 0xffff0000, v58
	s_waitcnt lgkmcnt(0)
	v_mov_b32_e32 v58, v52
	v_and_b32_e32 v61, 0xffff0000, v59
	v_pk_add_f32 v[32:33], v[32:33], 1.0 op_sel_hi:[1,0]
	v_lshlrev_b32_e32 v57, 16, v31
	v_lshlrev_b32_e32 v56, 16, v30
	v_mov_b32_e32 v59, v54
	v_pk_mul_f32 v[56:57], v[58:59], v[56:57]
	v_rcp_f32_e32 v33, v33
	s_nop 0
	v_mul_f32_e32 v33, v35, v33
	v_mul_f32_e32 v34, 0xbfb8aa3b, v62
	v_mul_f32_e32 v35, 0xbfb8aa3b, v61
	v_exp_f32_e32 v34, v34
	v_exp_f32_e32 v35, v35
	v_rcp_f32_e32 v32, v32
	s_nop 0
	v_mul_f32_e32 v32, v60, v32
	v_pk_mul_f32 v[32:33], v[32:33], v[56:57]
	v_mov_b32_e32 v54, v53
	v_pk_add_f32 v[34:35], v[34:35], 1.0 op_sel_hi:[1,0]
	v_and_b32_e32 v31, 0xffff0000, v31
	v_and_b32_e32 v30, 0xffff0000, v30
	v_pk_mul_f32 v[30:31], v[54:55], v[30:31]
	v_rcp_f32_e32 v35, v35
	s_nop 0
	v_mul_f32_e32 v35, v61, v35
	s_mov_b64 s[6:7], 0
	v_rcp_f32_e32 v34, v34
	s_nop 0
	v_mul_f32_e32 v34, v62, v34
	v_pk_mul_f32 v[30:31], v[34:35], v[30:31]
	v_cvt_pk_bf16_f32 v32, 0, v32
	v_cvt_pk_bf16_f32 v33, 0, v33
	v_cvt_pk_bf16_f32 v31, 0, v31
	v_cvt_pk_bf16_f32 v30, 0, v30
	v_and_b32_e32 v31, 0xffff0000, v31
	v_and_b32_e32 v30, 0xffff0000, v30
	v_or_b32_sdwa v31, v31, v33 dst_sel:DWORD dst_unused:UNUSED_PAD src0_sel:DWORD src1_sel:WORD_1
	v_or_b32_sdwa v30, v30, v32 dst_sel:DWORD dst_unused:UNUSED_PAD src0_sel:DWORD src1_sel:WORD_1
	global_store_dwordx4 v[50:51], v[28:31], off
	global_store_dwordx4 v[48:49], v[24:27], off
	global_store_dwordx4 v[46:47], v[20:23], off
	global_store_dwordx4 v[44:45], v[16:19], off
	global_store_dwordx4 v[42:43], v[12:15], off
	global_store_dwordx4 v[40:41], v[8:11], off
	global_store_dwordx4 v[38:39], v[4:7], off
	global_store_dwordx4 v[36:37], v[0:3], off
	s_barrier

; template <int DH, int MODE>
; __device__ void attn_item(const Params& p, int layer, int b, int blk, int head, char* smem) {
;     ...
;     V_SCATTER_(vr0, 0);
;     V_SCATTER_(vr1, 1);
;     if (KCH > 2) {
;       V_SCATTER_(vr2, 2);
;       V_SCATTER_(vr3, 3);
;     }
;     KV_LOAD_(it + 1);
;     if (!wskip) {
;       float4* s4 = reinterpret_cast<float4*>(Sf + row * SSTR + half * 32);
;       char* prow = Pb + half * 8192 + row * 64;
;       if (MODE == 0) {
;         const int kjb = kj0 + half * 32;
;         float tmax = -1e30f;
; #pragma unroll
;         for (int c = 0; c < 8; ++c) {
;           float4 v = s4[c];
;           float e[4] = {v.x, v.y, v.z, v.w};
; #pragma unroll
;           for (int k = 0; k < 4; ++k) {
;             int kj = kjb + c * 4 + k;
;             bool valid = (kj > row) && (kj <= row + 128);
;             tmax = valid ? fmaxf(tmax, e[k]) : tmax;
;           }
;         }
;         tmax = fmaxf(tmax, __shfl_xor(tmax, 1));
.LBB0_1129:
	s_or_b64 exec, exec, s[8:9]
	s_add_i32 s82, s82, 1
	s_min_i32 s8, s82, s80
	s_add_i32 s8, s8, s79
	s_lshl_b32 s8, s8, 6
	s_add_i32 s8, s8, s81
	s_ashr_i32 s9, s8, 31
	s_add_u32 s8, s8, s77
	s_addc_u32 s9, s9, 0
	s_waitcnt lgkmcnt(0)
	s_barrier
	ds_write_b16 v96, v48
	ds_write_b16_d16_hi v96, v48 offset:64
	ds_write_b16 v96, v49 offset:128
	ds_write_b16_d16_hi v96, v49 offset:192
	ds_write_b16 v96, v50 offset:256
	ds_write_b16_d16_hi v96, v50 offset:320
	ds_write_b16 v96, v51 offset:384
	ds_write_b16_d16_hi v96, v51 offset:448
	s_waitcnt vmcnt(0)
	ds_write_b16 v96, v52 offset:2048
	ds_write_b16_d16_hi v96, v52 offset:2112
	ds_write_b16 v96, v53 offset:2176
	ds_write_b16_d16_hi v96, v53 offset:2240
	ds_write_b16 v96, v54 offset:2304
	ds_write_b16_d16_hi v96, v54 offset:2368
	ds_write_b16 v96, v55 offset:2432
	ds_write_b16_d16_hi v96, v55 offset:2496
	v_lshl_add_u64 v[48:49], s[8:9], 0, v[66:67]
	v_mad_u64_u32 v[52:53], s[12:13], v48, s39, v[76:77]
	v_or_b32_e32 v48, s8, v72
	v_mad_i32_i24 v53, v49, s39, v53
	v_mad_u64_u32 v[54:55], s[12:13], v48, s39, v[78:79]
	v_add_co_u32_e32 v48, vcc, 0x4c000, v52
	v_mad_i32_i24 v55, s9, v160, v55
	s_nop 0
	v_addc_co_u32_e32 v49, vcc, 0, v53, vcc
	global_load_dwordx4 v[60:63], v[48:49], off
	s_nop 0
	global_load_dwordx4 v[48:51], v[54:55], off
	global_load_dwordx4 v[56:59], v[52:53], off
	s_nop 0
	global_load_dwordx4 v[52:55], v[54:55], off offset:64
	s_and_saveexec_b64 s[46:47], s[44:45]
	s_cbranch_execz .LBB0_1151
	v_add_u32_e32 v82, 0x4004, v90
	ds_read2_b32 v[82:83], v82 offset1:1
	ds_read_b32 v102, v90 offset:16396
	v_or_b32_e32 v101, s10, v89
	v_cmp_gt_i32_e32 vcc, v101, v74
	v_cmp_le_i32_e64 s[8:9], v101, v80
	s_and_b64 s[10:11], vcc, s[8:9]
	v_mov_b32_e32 v103, 0xf149f2ca
	s_and_saveexec_b64 s[8:9], s[10:11]
	s_cbranch_execz .LBB0_1132
	ds_read_b32 v103, v90 offset:16384
	s_waitcnt lgkmcnt(0)
	v_max_f32_e32 v103, 0xf149f2ca, v103
.LBB0_1132:
	s_or_b64 exec, exec, s[8:9]
	v_cmp_ge_i32_e32 vcc, v101, v74
	v_cmp_lt_i32_e64 s[8:9], v101, v80
	s_waitcnt lgkmcnt(1)
	v_max_f32_e32 v82, v103, v82
	s_and_b64 vcc, vcc, s[8:9]
	v_cndmask_b32_e32 v82, v103, v82, vcc
	v_or_b32_e32 v103, 2, v101
	v_cmp_gt_i32_e32 vcc, v103, v74
	v_cmp_le_i32_e64 s[8:9], v103, v80
	v_max_f32_e32 v83, v82, v83
	s_and_b64 vcc, vcc, s[8:9]
	v_cndmask_b32_e32 v82, v82, v83, vcc
	v_or_b32_e32 v83, 3, v101
	v_cmp_gt_i32_e32 vcc, v83, v74
	v_cmp_le_i32_e64 s[8:9], v83, v80
	s_waitcnt lgkmcnt(0)
	v_max_f32_e32 v83, v82, v102
	s_and_b64 vcc, vcc, s[8:9]
	v_cndmask_b32_e32 v103, v82, v83, vcc
	v_add_u32_e32 v82, 0x4014, v90
	ds_read2_b32 v[82:83], v82 offset1:1
	ds_read_b32 v102, v90 offset:16412
	v_or_b32_e32 v104, 4, v101
	v_cmp_gt_i32_e32 vcc, v104, v74
	v_cmp_le_i32_e64 s[8:9], v104, v80
	s_and_b64 s[10:11], vcc, s[8:9]
	s_and_saveexec_b64 s[8:9], s[10:11]
	s_cbranch_execz .LBB0_1134
	ds_read_b32 v104, v90 offset:16400
	s_waitcnt lgkmcnt(0)
	v_max_f32_e32 v103, v103, v104
.LBB0_1134:
	s_or_b64 exec, exec, s[8:9]
	v_or_b32_e32 v104, 5, v101
	v_cmp_gt_i32_e32 vcc, v104, v74
	v_cmp_le_i32_e64 s[8:9], v104, v80
	s_waitcnt lgkmcnt(1)
	v_max_f32_e32 v82, v103, v82
	s_and_b64 vcc, vcc, s[8:9]
	v_cndmask_b32_e32 v82, v103, v82, vcc
	v_or_b32_e32 v103, 6, v101
	v_cmp_gt_i32_e32 vcc, v103, v74
	v_cmp_le_i32_e64 s[8:9], v103, v80
	v_max_f32_e32 v83, v82, v83
	s_and_b64 vcc, vcc, s[8:9]
	v_cndmask_b32_e32 v82, v82, v83, vcc
	v_or_b32_e32 v83, 7, v101
	v_cmp_gt_i32_e32 vcc, v83, v74
	v_cmp_le_i32_e64 s[8:9], v83, v80
	s_waitcnt lgkmcnt(0)
	v_max_f32_e32 v83, v82, v102
	s_and_b64 vcc, vcc, s[8:9]
	v_cndmask_b32_e32 v103, v82, v83, vcc
	v_add_u32_e32 v82, 0x4024, v90
	ds_read2_b32 v[82:83], v82 offset1:1
	ds_read_b32 v102, v90 offset:16428
	v_or_b32_e32 v104, 8, v101
	v_cmp_gt_i32_e32 vcc, v104, v74
	v_cmp_le_i32_e64 s[8:9], v104, v80
	s_and_b64 s[10:11], vcc, s[8:9]
	s_and_saveexec_b64 s[8:9], s[10:11]
	s_cbranch_execz .LBB0_1136
	ds_read_b32 v104, v90 offset:16416
	s_waitcnt lgkmcnt(0)
	v_max_f32_e32 v103, v103, v104
.LBB0_1136:
	s_or_b64 exec, exec, s[8:9]
	v_or_b32_e32 v104, 9, v101
	v_cmp_gt_i32_e32 vcc, v104, v74
	v_cmp_le_i32_e64 s[8:9], v104, v80
	s_waitcnt lgkmcnt(1)
	v_max_f32_e32 v82, v103, v82
	s_and_b64 vcc, vcc, s[8:9]
	v_cndmask_b32_e32 v82, v103, v82, vcc
	v_or_b32_e32 v103, 10, v101
	v_cmp_gt_i32_e32 vcc, v103, v74
	v_cmp_le_i32_e64 s[8:9], v103, v80
	v_max_f32_e32 v83, v82, v83
	s_and_b64 vcc, vcc, s[8:9]
	v_cndmask_b32_e32 v82, v82, v83, vcc
	v_or_b32_e32 v83, 11, v101
	v_cmp_gt_i32_e32 vcc, v83, v74
	v_cmp_le_i32_e64 s[8:9], v83, v80
	s_waitcnt lgkmcnt(0)
	v_max_f32_e32 v83, v82, v102
	s_and_b64 vcc, vcc, s[8:9]
	v_cndmask_b32_e32 v103, v82, v83, vcc
	v_add_u32_e32 v82, 0x4034, v90
	ds_read2_b32 v[82:83], v82 offset1:1
	ds_read_b32 v102, v90 offset:16444
	v_or_b32_e32 v104, 12, v101
	v_cmp_gt_i32_e32 vcc, v104, v74
	v_cmp_le_i32_e64 s[8:9], v104, v80
	s_and_b64 s[10:11], vcc, s[8:9]
	s_and_saveexec_b64 s[8:9], s[10:11]
	s_cbranch_execz .LBB0_1138
	ds_read_b32 v104, v90 offset:16432
	s_waitcnt lgkmcnt(0)
	v_max_f32_e32 v103, v103, v104
.LBB0_1138:
	s_or_b64 exec, exec, s[8:9]
	v_or_b32_e32 v104, 13, v101
	v_cmp_gt_i32_e32 vcc, v104, v74
	v_cmp_le_i32_e64 s[8:9], v104, v80
	s_waitcnt lgkmcnt(1)
	v_max_f32_e32 v82, v103, v82
	s_and_b64 vcc, vcc, s[8:9]
	v_cndmask_b32_e32 v82, v103, v82, vcc
	v_or_b32_e32 v103, 14, v101
	v_cmp_gt_i32_e32 vcc, v103, v74
	v_cmp_le_i32_e64 s[8:9], v103, v80
	v_max_f32_e32 v83, v82, v83
	s_and_b64 vcc, vcc, s[8:9]
	v_cndmask_b32_e32 v82, v82, v83, vcc
	v_or_b32_e32 v83, 15, v101
	v_cmp_gt_i32_e32 vcc, v83, v74
	v_cmp_le_i32_e64 s[8:9], v83, v80
	s_waitcnt lgkmcnt(0)
	v_max_f32_e32 v83, v82, v102
	s_and_b64 vcc, vcc, s[8:9]
	v_cndmask_b32_e32 v103, v82, v83, vcc
	v_add_u32_e32 v82, 0x4044, v90
	ds_read2_b32 v[82:83], v82 offset1:1
	ds_read_b32 v102, v90 offset:16460
	v_or_b32_e32 v104, 16, v101
	v_cmp_gt_i32_e32 vcc, v104, v74
	v_cmp_le_i32_e64 s[8:9], v104, v80
	s_and_b64 s[10:11], vcc, s[8:9]
	s_and_saveexec_b64 s[8:9], s[10:11]
	s_cbranch_execz .LBB0_1140
	ds_read_b32 v104, v90 offset:16448
	s_waitcnt lgkmcnt(0)
	v_max_f32_e32 v103, v103, v104
; template <int DH, int MODE>
; __device__ void attn_item(const Params& p, int layer, int b, int blk, int head, char* smem) {
;     ...
; #pragma unroll
;         for (int c = 0; c < 8; ++c) {
;           float4 v = s4[c];
;           float e[4] = {v.x, v.y, v.z, v.w};
; #pragma unroll
;           for (int k = 0; k < 4; ++k) {
;             int kj = kjb + c * 4 + k;
;             bool valid = (kj > row) && (kj <= row + 128);
;             tmax = valid ? fmaxf(tmax, e[k]) : tmax;
;           }
;         }
;         tmax = fmaxf(tmax, __shfl_xor(tmax, 1));
;         float m_new = fmaxf(m_run, tmax);
.LBB0_1140:
	s_or_b64 exec, exec, s[8:9]
	v_or_b32_e32 v104, 17, v101
	v_cmp_gt_i32_e32 vcc, v104, v74
	v_cmp_le_i32_e64 s[8:9], v104, v80
	s_waitcnt lgkmcnt(1)
	v_max_f32_e32 v82, v103, v82
	s_and_b64 vcc, vcc, s[8:9]
	v_cndmask_b32_e32 v82, v103, v82, vcc
	v_or_b32_e32 v103, 18, v101
	v_cmp_gt_i32_e32 vcc, v103, v74
	v_cmp_le_i32_e64 s[8:9], v103, v80
	v_max_f32_e32 v83, v82, v83
	s_and_b64 vcc, vcc, s[8:9]
	v_cndmask_b32_e32 v82, v82, v83, vcc
	v_or_b32_e32 v83, 19, v101
	v_cmp_gt_i32_e32 vcc, v83, v74
	v_cmp_le_i32_e64 s[8:9], v83, v80
	s_waitcnt lgkmcnt(0)
	v_max_f32_e32 v83, v82, v102
	s_and_b64 vcc, vcc, s[8:9]
	v_cndmask_b32_e32 v103, v82, v83, vcc
	v_add_u32_e32 v82, 0x4054, v90
	ds_read2_b32 v[82:83], v82 offset1:1
	ds_read_b32 v102, v90 offset:16476
	v_or_b32_e32 v104, 20, v101
	v_cmp_gt_i32_e32 vcc, v104, v74
	v_cmp_le_i32_e64 s[8:9], v104, v80
	s_and_b64 s[10:11], vcc, s[8:9]
	s_and_saveexec_b64 s[8:9], s[10:11]
	s_cbranch_execz .LBB0_1142
	ds_read_b32 v104, v90 offset:16464
	s_waitcnt lgkmcnt(0)
	v_max_f32_e32 v103, v103, v104
.LBB0_1142:
	s_or_b64 exec, exec, s[8:9]
	v_or_b32_e32 v104, 21, v101
	v_cmp_gt_i32_e32 vcc, v104, v74
	v_cmp_le_i32_e64 s[8:9], v104, v80
	s_waitcnt lgkmcnt(1)
	v_max_f32_e32 v82, v103, v82
	s_and_b64 vcc, vcc, s[8:9]
	v_cndmask_b32_e32 v82, v103, v82, vcc
	v_or_b32_e32 v103, 22, v101
	v_cmp_gt_i32_e32 vcc, v103, v74
	v_cmp_le_i32_e64 s[8:9], v103, v80
	v_max_f32_e32 v83, v82, v83
	s_and_b64 vcc, vcc, s[8:9]
	v_cndmask_b32_e32 v82, v82, v83, vcc
	v_or_b32_e32 v83, 23, v101
	v_cmp_gt_i32_e32 vcc, v83, v74
	v_cmp_le_i32_e64 s[8:9], v83, v80
	s_waitcnt lgkmcnt(0)
	v_max_f32_e32 v83, v82, v102
	s_and_b64 vcc, vcc, s[8:9]
	v_cndmask_b32_e32 v103, v82, v83, vcc
	v_add_u32_e32 v82, 0x4064, v90
	ds_read2_b32 v[82:83], v82 offset1:1
	ds_read_b32 v102, v90 offset:16492
	v_or_b32_e32 v104, 24, v101
	v_cmp_gt_i32_e32 vcc, v104, v74
	v_cmp_le_i32_e64 s[8:9], v104, v80
	s_and_b64 s[10:11], vcc, s[8:9]
	s_and_saveexec_b64 s[8:9], s[10:11]
	s_cbranch_execz .LBB0_1144
	ds_read_b32 v104, v90 offset:16480
	s_waitcnt lgkmcnt(0)
	v_max_f32_e32 v103, v103, v104
.LBB0_1144:
	s_or_b64 exec, exec, s[8:9]
	v_or_b32_e32 v104, 25, v101
	v_cmp_gt_i32_e32 vcc, v104, v74
	v_cmp_le_i32_e64 s[8:9], v104, v80
	s_waitcnt lgkmcnt(1)
	v_max_f32_e32 v82, v103, v82
	s_and_b64 vcc, vcc, s[8:9]
	v_cndmask_b32_e32 v82, v103, v82, vcc
	v_or_b32_e32 v103, 26, v101
	v_cmp_gt_i32_e32 vcc, v103, v74
	v_cmp_le_i32_e64 s[8:9], v103, v80
	v_max_f32_e32 v83, v82, v83
	s_and_b64 vcc, vcc, s[8:9]
	v_cndmask_b32_e32 v82, v82, v83, vcc
	v_or_b32_e32 v83, 27, v101
	v_cmp_gt_i32_e32 vcc, v83, v74
	v_cmp_le_i32_e64 s[8:9], v83, v80
	s_waitcnt lgkmcnt(0)
	v_max_f32_e32 v83, v82, v102
	s_and_b64 vcc, vcc, s[8:9]
	v_cndmask_b32_e32 v103, v82, v83, vcc
	v_add_u32_e32 v82, 0x4074, v90
	ds_read2_b32 v[82:83], v82 offset1:1
	ds_read_b32 v102, v90 offset:16508
	v_or_b32_e32 v104, 28, v101
	v_cmp_gt_i32_e32 vcc, v104, v74
	v_cmp_le_i32_e64 s[8:9], v104, v80
	s_and_b64 s[10:11], vcc, s[8:9]
	s_and_saveexec_b64 s[8:9], s[10:11]
	s_cbranch_execz .LBB0_1146
	ds_read_b32 v104, v90 offset:16496
	s_waitcnt lgkmcnt(0)
	v_max_f32_e32 v103, v103, v104
.LBB0_1146:
	s_or_b64 exec, exec, s[8:9]
	v_or_b32_e32 v104, 29, v101
	v_cmp_gt_i32_e32 vcc, v104, v74
	v_cmp_le_i32_e64 s[8:9], v104, v80
	s_waitcnt lgkmcnt(1)
	v_max_f32_e32 v82, v103, v82
	s_and_b64 vcc, vcc, s[8:9]
	v_cndmask_b32_e32 v82, v103, v82, vcc
	v_or_b32_e32 v103, 30, v101
	v_cmp_gt_i32_e32 vcc, v103, v74
	v_cmp_le_i32_e64 s[8:9], v103, v80
	v_max_f32_e32 v83, v82, v83
	s_and_b64 vcc, vcc, s[8:9]
	v_cndmask_b32_e32 v82, v82, v83, vcc
	v_or_b32_e32 v83, 31, v101
	v_cmp_gt_i32_e32 vcc, v83, v74
	v_cmp_le_i32_e64 s[8:9], v83, v80
	s_waitcnt lgkmcnt(0)
	v_max_f32_e32 v83, v82, v102
	s_and_b64 vcc, vcc, s[8:9]
	v_cndmask_b32_e32 v82, v82, v83, vcc
	v_cmp_lt_i32_e32 vcc, v157, v158
	s_mov_b32 s83, 0
	v_mov_b32_e32 v103, 0
	v_cndmask_b32_e32 v83, v156, v157, vcc
	v_lshlrev_b32_e32 v83, 2, v83
	ds_bpermute_b32 v101, v83, v82
	v_mov_b32_e32 v102, v91
	s_waitcnt lgkmcnt(0)
	v_max3_f32 v82, v87, v82, v101
	v_mov_b32_e32 v101, v93
; __device__ __forceinline__ unsigned pack2(float a, float b) { return (unsigned)f2bf(a) | ((unsigned)f2bf(b) << 16); }
; template <int DH, int MODE>
; __device__ void attn_item(const Params& p, int layer, int b, int blk, int head, char* smem) {
;     ...
;         float alpha = __builtin_amdgcn_exp2f(m_run - m_new);
;         float psum = 0.f;
; #pragma unroll 2
;         for (int s8 = 0; s8 < 4; ++s8) {
;           float4 va = s4[2 * s8], vb = s4[2 * s8 + 1];
;           float e[8] = {va.x, va.y, va.z, va.w, vb.x, vb.y, vb.z, vb.w};
;           float pv[8];
; #pragma unroll
;           for (int k = 0; k < 8; ++k) {
;             int kj = kjb + s8 * 8 + k;
;             bool valid = (kj > row) && (kj <= row + 128);
;             float pe = valid ? __builtin_amdgcn_exp2f(e[k] - m_new) : 0.f;
;             pv[k] = pe;
;             psum += pe;
;           }
;           uint4 ov;
;           ov.x = pack2(pv[0], pv[1]); ov.y = pack2(pv[2], pv[3]);
;           ov.z = pack2(pv[4], pv[5]); ov.w = pack2(pv[6], pv[7]);
;           *reinterpret_cast<uint4*>(prow + s8 * 16) = ov;
;         }
;         psum += __shfl_xor(psum, 1);
;         l_run = l_run * alpha + psum;
;         m_run = m_new;
;         if (half == 0) alpha_s[row] = alpha;
.LBB0_1147:
	ds_read_b128 v[104:107], v102
	ds_read_b128 v[108:111], v102 offset:16
	v_add_u32_e32 v112, s83, v92
	v_add_u32_e32 v113, 2, v112
	v_cmp_gt_i32_e64 s[8:9], v112, v74
	s_waitcnt lgkmcnt(1)
	v_sub_f32_e32 v104, v104, v82
	v_exp_f32_e32 v104, v104
	v_sub_f32_e32 v106, v106, v82
	v_sub_f32_e32 v105, v105, v82
	v_exp_f32_e32 v106, v106
	v_exp_f32_e32 v105, v105
	v_sub_f32_e32 v107, v107, v82
	v_cmp_le_i32_e64 s[12:13], v112, v80
	v_exp_f32_e32 v107, v107
	v_cmp_gt_i32_e32 vcc, v113, v65
	v_cmp_le_i32_e64 s[10:11], v113, v69
	s_and_b64 s[8:9], s[8:9], s[12:13]
	v_add_u32_e32 v114, 3, v112
	s_and_b64 vcc, vcc, s[10:11]
	v_cndmask_b32_e64 v104, 0, v104, s[8:9]
	v_cmp_lt_i32_e64 s[8:9], v112, v80
	v_cmp_ge_i32_e64 s[12:13], v112, v74
	v_cndmask_b32_e32 v106, 0, v106, vcc
	v_cmp_lt_i32_e32 vcc, v74, v114
	v_cmp_ge_i32_e64 s[10:11], v80, v114
	s_and_b64 s[8:9], s[8:9], s[12:13]
	v_add_f32_e32 v103, v103, v104
	s_and_b64 vcc, vcc, s[10:11]
	v_cndmask_b32_e64 v105, 0, v105, s[8:9]
	v_cndmask_b32_e32 v107, 0, v107, vcc
	v_add_f32_e32 v103, v103, v105
	v_add_f32_e32 v103, v103, v106
	v_cvt_pk_bf16_f32 v106, 0, v106
	s_waitcnt lgkmcnt(0)
	v_sub_f32_e32 v108, v108, v82
	v_sub_f32_e32 v110, v110, v82
	v_add_f32_e32 v103, v103, v107
	v_cvt_pk_bf16_f32 v104, 0, v104
	v_cvt_pk_bf16_f32 v107, 0, v107
	v_exp_f32_e32 v108, v108
	v_exp_f32_e32 v110, v110
	v_cvt_pk_bf16_f32 v105, 0, v105
	v_and_b32_e32 v107, 0xffff0000, v107
	v_sub_f32_e32 v109, v109, v82
	v_sub_f32_e32 v111, v111, v82
	v_and_b32_e32 v113, 0xffff0000, v105
	v_or_b32_sdwa v105, v107, v106 dst_sel:DWORD dst_unused:UNUSED_PAD src0_sel:DWORD src1_sel:WORD_1
	v_or_b32_e32 v106, 6, v112
	v_or_b32_e32 v107, 4, v112
	v_exp_f32_e32 v109, v109
	v_exp_f32_e32 v111, v111
	v_cmp_gt_i32_e32 vcc, v107, v74
	v_cmp_gt_i32_e64 s[8:9], v106, v65
	v_cmp_le_i32_e64 s[10:11], v107, v80
	v_cmp_le_i32_e64 s[12:13], v106, v69
	s_and_b64 s[8:9], s[8:9], s[12:13]
	s_and_b64 vcc, vcc, s[10:11]
	v_or_b32_e32 v106, 7, v112
	v_or_b32_e32 v107, 5, v112
	v_cndmask_b32_e32 v108, 0, v108, vcc
	v_cndmask_b32_e64 v110, 0, v110, s[8:9]
	v_cmp_gt_i32_e32 vcc, v107, v74
	v_cmp_gt_i32_e64 s[8:9], v106, v65
	v_cmp_le_i32_e64 s[10:11], v107, v80
	v_cmp_le_i32_e64 s[12:13], v106, v69
	s_and_b64 s[8:9], s[8:9], s[12:13]
	s_and_b64 vcc, vcc, s[10:11]
	v_cndmask_b32_e32 v109, 0, v109, vcc
	v_cndmask_b32_e64 v111, 0, v111, s[8:9]
	v_or_b32_sdwa v104, v113, v104 dst_sel:DWORD dst_unused:UNUSED_PAD src0_sel:DWORD src1_sel:WORD_1
	v_cvt_pk_bf16_f32 v113, 0, v108
	v_cvt_pk_bf16_f32 v107, 0, v111
	v_cvt_pk_bf16_f32 v114, 0, v109
	v_cvt_pk_bf16_f32 v106, 0, v110
	v_and_b32_e32 v107, 0xffff0000, v107
	v_and_b32_e32 v114, 0xffff0000, v114
	v_add_f32_e32 v103, v103, v108
	v_or_b32_sdwa v107, v107, v106 dst_sel:DWORD dst_unused:UNUSED_PAD src0_sel:DWORD src1_sel:WORD_1
	v_or_b32_sdwa v106, v114, v113 dst_sel:DWORD dst_unused:UNUSED_PAD src0_sel:DWORD src1_sel:WORD_1
	v_add_f32_e32 v103, v103, v109
	v_add_f32_e32 v103, v103, v110
	ds_write_b128 v101, v[104:107]
	v_add_f32_e32 v103, v103, v111
	ds_read_b128 v[104:107], v102 offset:32
	ds_read_b128 v[108:111], v102 offset:48
	v_add_u32_e32 v113, 8, v112
	v_add_u32_e32 v114, 10, v112
	v_cmp_gt_i32_e64 s[8:9], v113, v74
	s_waitcnt lgkmcnt(1)
	v_sub_f32_e32 v104, v104, v82
	v_exp_f32_e32 v104, v104
	v_sub_f32_e32 v106, v106, v82
	v_sub_f32_e32 v105, v105, v82
	v_exp_f32_e32 v106, v106
	v_exp_f32_e32 v105, v105
	v_sub_f32_e32 v107, v107, v82
	v_cmp_le_i32_e64 s[12:13], v113, v80
	v_exp_f32_e32 v107, v107
	v_cmp_gt_i32_e32 vcc, v114, v65
	v_cmp_le_i32_e64 s[10:11], v114, v69
	s_and_b64 s[8:9], s[8:9], s[12:13]
	v_add_u32_e32 v112, 11, v112
	s_and_b64 vcc, vcc, s[10:11]
	v_cndmask_b32_e64 v104, 0, v104, s[8:9]
	v_cmp_lt_i32_e64 s[8:9], v113, v80
	v_cmp_ge_i32_e64 s[12:13], v113, v74
	v_cndmask_b32_e32 v106, 0, v106, vcc
	v_cmp_lt_i32_e32 vcc, v74, v112
	v_cmp_ge_i32_e64 s[10:11], v80, v112
	s_and_b64 s[8:9], s[8:9], s[12:13]
	v_add_f32_e32 v103, v103, v104
	s_and_b64 vcc, vcc, s[10:11]
	v_cndmask_b32_e64 v105, 0, v105, s[8:9]
	v_cndmask_b32_e32 v107, 0, v107, vcc
	v_add_f32_e32 v103, v103, v105
	v_add_f32_e32 v103, v103, v106
	v_cvt_pk_bf16_f32 v106, 0, v106
	s_waitcnt lgkmcnt(0)
	v_sub_f32_e32 v108, v108, v82
	v_sub_f32_e32 v110, v110, v82
	v_add_f32_e32 v103, v103, v107
	v_cvt_pk_bf16_f32 v104, 0, v104
	v_cvt_pk_bf16_f32 v107, 0, v107
	v_exp_f32_e32 v108, v108
	v_exp_f32_e32 v110, v110
	v_cvt_pk_bf16_f32 v105, 0, v105
	v_and_b32_e32 v107, 0xffff0000, v107
	v_sub_f32_e32 v109, v109, v82
	v_sub_f32_e32 v111, v111, v82
	v_and_b32_e32 v112, 0xffff0000, v105
	v_or_b32_sdwa v105, v107, v106 dst_sel:DWORD dst_unused:UNUSED_PAD src0_sel:DWORD src1_sel:WORD_1
	v_or_b32_e32 v106, 6, v113
	v_or_b32_e32 v107, 4, v113
	v_exp_f32_e32 v109, v109
	v_exp_f32_e32 v111, v111
	v_cmp_gt_i32_e32 vcc, v107, v74
	v_cmp_gt_i32_e64 s[8:9], v106, v65
	v_cmp_le_i32_e64 s[10:11], v107, v80
	v_cmp_le_i32_e64 s[12:13], v106, v69
	s_and_b64 s[8:9], s[8:9], s[12:13]
	s_and_b64 vcc, vcc, s[10:11]
	v_or_b32_e32 v106, 7, v113
	v_or_b32_e32 v107, 5, v113
	v_cndmask_b32_e32 v108, 0, v108, vcc
	v_cndmask_b32_e64 v110, 0, v110, s[8:9]
	v_cmp_gt_i32_e32 vcc, v107, v74
	v_cmp_gt_i32_e64 s[8:9], v106, v65
	v_cmp_le_i32_e64 s[10:11], v107, v80
	v_cmp_le_i32_e64 s[12:13], v106, v69
	s_and_b64 s[8:9], s[8:9], s[12:13]
	s_and_b64 vcc, vcc, s[10:11]
	v_cndmask_b32_e32 v109, 0, v109, vcc
	v_cndmask_b32_e64 v111, 0, v111, s[8:9]
	v_or_b32_sdwa v104, v112, v104 dst_sel:DWORD dst_unused:UNUSED_PAD src0_sel:DWORD src1_sel:WORD_1
	v_cvt_pk_bf16_f32 v112, 0, v108
	v_cvt_pk_bf16_f32 v107, 0, v111
	v_cvt_pk_bf16_f32 v113, 0, v109
	v_add_f32_e32 v103, v103, v108
	v_cvt_pk_bf16_f32 v106, 0, v110
	v_and_b32_e32 v107, 0xffff0000, v107
	v_and_b32_e32 v113, 0xffff0000, v113
	v_add_f32_e32 v103, v103, v109
	v_or_b32_sdwa v107, v107, v106 dst_sel:DWORD dst_unused:UNUSED_PAD src0_sel:DWORD src1_sel:WORD_1
	v_or_b32_sdwa v106, v113, v112 dst_sel:DWORD dst_unused:UNUSED_PAD src0_sel:DWORD src1_sel:WORD_1
	v_add_f32_e32 v103, v103, v110
	s_add_i32 s83, s83, 16
	v_add_f32_e32 v103, v103, v111
	ds_write_b128 v101, v[104:107] offset:16
	v_add_u32_e32 v102, 64, v102
	v_add_u32_e32 v101, 32, v101
	s_cmp_eq_u32 s83, 32
	s_cbranch_scc0 .LBB0_1147
	v_sub_f32_e32 v101, v87, v82
	ds_bpermute_b32 v87, v83, v103
	v_exp_f32_e32 v83, v101
	s_and_saveexec_b64 s[8:9], s[6:7]
	ds_write_b32 v97, v83 offset:8192
	s_or_b64 exec, exec, s[8:9]
	s_waitcnt lgkmcnt(0)
	v_add_f32_e32 v101, v103, v87
	v_fmac_f32_e32 v101, v88, v83
	v_mov_b32_e32 v87, v82
	v_mov_b32_e32 v88, v101

; template <int DH, int MODE>
; __device__ void attn_item(const Params& p, int layer, int b, int blk, int head, char* smem) {
;     ...
;   if (MODE == 0 && half == 0) linv_s[row] = 1.f / l_run;
;   __syncthreads();
;   {
;     constexpr int OST = DH + 4;
;     constexpr int CPR = DH / 8;
;     constexpr int NCH = 128 * CPR / 256;
;     float* Of = reinterpret_cast<float*>(smem);
;     uint4 gt[NCH];
; #pragma unroll
;     for (int i = 0; i < NCH; ++i) {
;       int q = tid + 256 * i, r = q / CPR, c = (q % CPR) * 8;
;       gt[i] = *reinterpret_cast<const uint4*>(P + (tq0 + r) * NP + gcol + c);
;     }
;     float lis[2][4];
; #pragma unroll
;     for (int m = 0; m < 2; ++m)
; #pragma unroll
;       for (int j = 0; j < 4; ++j) lis[m][j] = (MODE == 0) ? linv_s[wid * 32 + m * 16 + fq * 4 + j] : 1.f;
;     if (MODE == 0) __syncthreads();
; #pragma unroll
;     for (int m = 0; m < 2; ++m)
; #pragma unroll
;       for (int j = 0; j < 4; ++j) {
;         int r = wid * 32 + m * 16 + fq * 4 + j;
; #pragma unroll
;         for (int n = 0; n < NDT; ++n) Of[r * OST + n * 16 + fr] = o[m][n][j] * lis[m][j];
.LBB0_1153:
	v_readfirstlane_b32 s10, v85
	s_and_saveexec_b64 s[8:9], s[6:7]
	s_cbranch_execz .LBB0_1155
	v_rcp_f32_e32 v32, v88
	v_lshlrev_b32_e32 v33, 2, v74
	ds_write_b32 v33, v32 offset:8704
.LBB0_1155:
	s_or_b64 exec, exec, s[8:9]
	v_lshl_add_u64 v[44:45], v[66:67], 0, s[16:17]
	v_mov_b64_e32 v[46:47], s[42:43]
	v_mad_u64_u32 v[32:33], s[8:9], v44, s39, v[46:47]
	v_mad_i32_i24 v33, v45, s39, v33
	v_lshl_add_u64 v[36:37], v[32:33], 0, v[70:71]
	v_add_u32_e32 v32, 0x100, v81
	v_ashrrev_i32_e32 v33, 31, v32
	v_lshrrev_b32_e32 v33, 29, v33
	v_add_u32_e32 v33, v32, v33
	v_ashrrev_i32_e32 v86, 3, v33
	v_and_b32_e32 v33, -8, v33
	v_sub_u32_e32 v85, v32, v33
	v_lshlrev_b32_e32 v32, 3, v85
	v_ashrrev_i32_e32 v33, 31, v32
	s_waitcnt vmcnt(2)
	v_add_u32_e32 v48, 0x200, v81
	v_lshlrev_b64 v[90:91], 1, v[32:33]
	v_ashrrev_i32_e32 v32, 31, v48
	v_lshrrev_b32_e32 v32, 29, v32
	v_add_u32_e32 v32, v48, v32
	v_ashrrev_i32_e32 v92, 3, v32
	v_and_b32_e32 v49, -8, v32
	v_add_u32_e32 v32, 0x300, v81
	v_ashrrev_i32_e32 v33, 31, v32
	v_lshrrev_b32_e32 v33, 29, v33
	v_ashrrev_i32_e32 v87, 31, v86
	v_add_u32_e32 v33, v32, v33
	v_lshl_add_u64 v[88:89], v[86:87], 0, s[16:17]
	v_ashrrev_i32_e32 v94, 3, v33
	v_and_b32_e32 v33, -8, v33
	v_mad_u64_u32 v[34:35], s[8:9], v88, s39, v[46:47]
	v_sub_u32_e32 v87, v32, v33
	v_ashrrev_i32_e32 v95, 31, v94
	v_mad_i32_i24 v35, v89, s39, v35
	v_lshlrev_b32_e32 v32, 3, v87
	v_lshl_add_u64 v[40:41], v[94:95], 0, s[16:17]
	v_lshl_add_u64 v[38:39], v[34:35], 0, v[90:91]
	v_mad_u64_u32 v[34:35], s[8:9], v40, s39, v[46:47]
	v_ashrrev_i32_e32 v33, 31, v32
	v_mad_i32_i24 v35, v41, s39, v35
	v_lshlrev_b64 v[42:43], 1, v[32:33]
	v_lshl_add_u64 v[32:33], v[34:35], 0, v[42:43]
	v_add_co_u32_e32 v32, vcc, s65, v32
	s_waitcnt lgkmcnt(0)
	s_nop 0
	v_addc_co_u32_e32 v33, vcc, 0, v33, vcc
	s_barrier
	global_load_dwordx4 v[32:35], v[32:33], off offset:512
	v_sub_u32_e32 v95, v48, v49
	v_ashrrev_i32_e32 v93, 31, v92
	v_lshlrev_b32_e32 v48, 3, v95
	v_lshl_add_u64 v[96:97], v[92:93], 0, s[16:17]
	v_mad_u64_u32 v[46:47], s[8:9], v96, s39, v[46:47]
	v_ashrrev_i32_e32 v49, 31, v48
	v_mad_i32_i24 v47, v97, s39, v47
	v_lshlrev_b64 v[98:99], 1, v[48:49]
	v_lshl_add_u64 v[100:101], v[46:47], 0, v[98:99]
	v_lshl_or_b32 v46, v75, 7, v128
	ds_read_b128 v[60:63], v46 offset:8704
	ds_read_b128 v[80:83], v46 offset:8768
	s_ashr_i32 s7, s10, 31
	s_add_u32 s6, s28, s10
	s_addc_u32 s7, s29, s7
	s_lshl_b32 s8, s76, 1
	s_add_u32 s6, s6, s8
	v_lshl_or_b32 v46, v84, 2, v64
	s_waitcnt lgkmcnt(0)
	v_mul_f32_e32 v69, v0, v80
	s_addc_u32 s7, s7, 0
	v_mul_lo_u32 v0, v66, s67
	v_mul_lo_u32 v46, v46, s67
	v_mul_f32_e32 v75, v1, v81
	v_lshl_add_u32 v66, v68, 2, v0
	v_mov_b64_e32 v[0:1], s[6:7]
	v_lshl_add_u32 v47, v73, 2, v46
	v_mul_f32_e32 v48, v16, v60
	v_mul_f32_e32 v49, v28, v60
	v_mul_f32_e32 v50, v24, v60
	v_mul_f32_e32 v51, v20, v60
	s_waitcnt vmcnt(1)
	v_mul_f32_e32 v52, v17, v61
	v_mul_f32_e32 v53, v29, v61
	v_mul_f32_e32 v54, v25, v61
	v_mul_f32_e32 v55, v21, v61
	v_mul_f32_e32 v56, v18, v62
	v_mul_f32_e32 v57, v30, v62
	v_mul_f32_e32 v58, v26, v62
	v_mul_f32_e32 v59, v22, v62
	v_mul_f32_e32 v60, v19, v63
	v_mul_f32_e32 v61, v31, v63
	v_mul_f32_e32 v62, v27, v63
	v_mul_f32_e32 v64, v23, v63
	v_mul_f32_e32 v63, v12, v80
	v_mul_f32_e32 v65, v8, v80
	v_mul_f32_e32 v67, v4, v80
	v_mul_f32_e32 v72, v13, v81
	v_mul_f32_e32 v73, v9, v81
	v_mul_f32_e32 v74, v5, v81
	v_mul_f32_e32 v76, v14, v82
	v_mul_f32_e32 v77, v10, v82
	v_mul_f32_e32 v78, v6, v82
	v_mul_f32_e32 v80, v2, v82
	v_mul_f32_e32 v79, v15, v83
	v_mul_f32_e32 v81, v11, v83
	v_mul_f32_e32 v82, v7, v83
	v_mul_f32_e32 v83, v3, v83
	v_mad_u64_u32 v[2:3], s[6:7], v44, s63, v[0:1]
	v_mad_i32_i24 v3, v45, s63, v3
	v_lshl_add_u64 v[12:13], v[2:3], 0, v[70:71]
	v_mul_lo_u32 v2, v86, s67
	v_lshl_add_u32 v46, v85, 5, v2
	v_mad_u64_u32 v[2:3], s[6:7], v88, s63, v[0:1]
	v_mad_i32_i24 v3, v89, s63, v3
	v_mad_u64_u32 v[4:5], s[6:7], v40, s63, v[0:1]
	v_lshl_add_u64 v[10:11], v[2:3], 0, v[90:91]
	v_mul_lo_u32 v2, v92, s67
	v_mad_i32_i24 v5, v41, s63, v5
	v_lshl_add_u32 v45, v95, 5, v2
	v_mad_u64_u32 v[2:3], s[6:7], v96, s63, v[0:1]
	v_lshl_add_u64 v[14:15], v[4:5], 0, v[42:43]
	v_mad_i32_i24 v3, v97, s63, v3
	v_add_co_u32_e32 v0, vcc, s65, v100
	v_lshl_add_u64 v[8:9], v[2:3], 0, v[98:99]
	v_mul_lo_u32 v2, v94, s67
	s_waitcnt vmcnt(0)
	v_lshlrev_b32_e32 v16, 16, v33
	v_lshlrev_b32_e32 v18, 16, v32
	v_mul_f32_e32 v6, 0xbfb8aa3b, v18
	v_mul_f32_e32 v7, 0xbfb8aa3b, v16
	v_exp_f32_e32 v6, v6
	v_exp_f32_e32 v7, v7
	v_addc_co_u32_e32 v1, vcc, 0, v101, vcc
	v_lshl_add_u32 v44, v87, 5, v2
	v_pk_add_f32 v[4:5], v[6:7], 1.0 op_sel_hi:[1,0]
	global_load_dwordx4 v[0:3], v[0:1], off offset:512
	v_and_b32_e32 v19, 0xffff0000, v33
	v_and_b32_e32 v20, 0xffff0000, v32
	v_mul_f32_e32 v6, 0xbfb8aa3b, v20
	v_rcp_f32_e32 v17, v5
	s_nop 0
	v_mul_f32_e32 v17, v16, v17
	v_mul_f32_e32 v7, 0xbfb8aa3b, v19
	v_exp_f32_e32 v6, v6
	v_exp_f32_e32 v7, v7
	s_nop 0
	v_pk_add_f32 v[6:7], v[6:7], 1.0 op_sel_hi:[1,0]
	v_rcp_f32_e32 v16, v4
	s_nop 0
	v_mul_f32_e32 v16, v18, v16
	v_lshlrev_b32_e32 v23, 16, v34
	v_rcp_f32_e32 v4, v7
	s_nop 0
	v_mul_f32_e32 v19, v19, v4
	v_lshlrev_b32_e32 v22, 16, v35
	v_mul_f32_e32 v4, 0xbfb8aa3b, v23
	v_mul_f32_e32 v5, 0xbfb8aa3b, v22
	v_exp_f32_e32 v4, v4
	v_exp_f32_e32 v5, v5
	v_rcp_f32_e32 v18, v6
	s_nop 0
	v_mul_f32_e32 v18, v20, v18
	v_and_b32_e32 v24, 0xffff0000, v35
	v_pk_add_f32 v[4:5], v[4:5], 1.0 op_sel_hi:[1,0]
	v_and_b32_e32 v25, 0xffff0000, v34
	v_mul_f32_e32 v6, 0xbfb8aa3b, v25
	v_exp_f32_e32 v6, v6
	v_rcp_f32_e32 v21, v5
	s_nop 0
	v_mul_f32_e32 v21, v22, v21
	v_mul_f32_e32 v7, 0xbfb8aa3b, v24
	v_exp_f32_e32 v7, v7
	s_nop 0
	v_pk_add_f32 v[6:7], v[6:7], 1.0 op_sel_hi:[1,0]
	v_rcp_f32_e32 v20, v4
	s_nop 0
	v_mul_f32_e32 v20, v23, v20
	v_rcp_f32_e32 v23, v7
	s_nop 0
	v_mul_f32_e32 v23, v24, v23
	s_waitcnt vmcnt(0)
; __device__ __forceinline__ unsigned pack2(float a, float b) { return (unsigned)f2bf(a) | ((unsigned)f2bf(b) << 16); }
; __device__ __forceinline__ float bflo(unsigned w) { return __uint_as_float(w << 16); }
; __device__ __forceinline__ float bfhi(unsigned w) { return __uint_as_float(w & 0xffff0000u); }
; __device__ __forceinline__ float silu_f(float g) { return g / (1.f + __expf(-g)); }
; template <int DH, int MODE>
; __device__ void attn_item(const Params& p, int layer, int b, int blk, int head, char* smem) {
;     ...
;     constexpr int NCH = 128 * CPR / 256;
;     float* Of = reinterpret_cast<float*>(smem);
;     uint4 gt[NCH];
; #pragma unroll
;     for (int i = 0; i < NCH; ++i) {
;       int q = tid + 256 * i, r = q / CPR, c = (q % CPR) * 8;
;       gt[i] = *reinterpret_cast<const uint4*>(P + (tq0 + r) * NP + gcol + c);
;     }
;     float lis[2][4];
; #pragma unroll
;     for (int m = 0; m < 2; ++m)
; #pragma unroll
;       for (int j = 0; j < 4; ++j) lis[m][j] = (MODE == 0) ? linv_s[wid * 32 + m * 16 + fq * 4 + j] : 1.f;
;     if (MODE == 0) __syncthreads();
; #pragma unroll
;     for (int m = 0; m < 2; ++m)
; #pragma unroll
;       for (int j = 0; j < 4; ++j) {
;         int r = wid * 32 + m * 16 + fq * 4 + j;
; #pragma unroll
;         for (int n = 0; n < NDT; ++n) Of[r * OST + n * 16 + fr] = o[m][n][j] * lis[m][j];
;       }
;     __syncthreads();
;     ...
;         ow[e] = pack2(mm[2 * e] * silu_f(bflo(gw[e])), mm[2 * e + 1] * silu_f(bfhi(gw[e])));
	v_lshlrev_b32_e32 v24, 16, v1
	v_lshlrev_b32_e32 v26, 16, v0
	v_mul_f32_e32 v4, 0xbfb8aa3b, v26
	v_mul_f32_e32 v5, 0xbfb8aa3b, v24
	v_exp_f32_e32 v4, v4
	v_exp_f32_e32 v5, v5
	v_and_b32_e32 v27, 0xffff0000, v1
	v_rcp_f32_e32 v22, v6
	s_nop 0
	v_mul_f32_e32 v22, v25, v22
	v_pk_add_f32 v[4:5], v[4:5], 1.0 op_sel_hi:[1,0]
	v_and_b32_e32 v28, 0xffff0000, v0
	v_mul_f32_e32 v0, 0xbfb8aa3b, v28
	v_exp_f32_e32 v6, v0
	v_lshlrev_b32_e32 v32, 16, v3
	v_mul_f32_e32 v7, 0xbfb8aa3b, v27
	v_rcp_f32_e32 v1, v5
	s_nop 0
	v_mul_f32_e32 v1, v24, v1
	v_exp_f32_e32 v7, v7
	s_nop 0
	v_pk_add_f32 v[24:25], v[6:7], 1.0 op_sel_hi:[1,0]
	v_rcp_f32_e32 v0, v4
	s_nop 0
	v_mul_f32_e32 v0, v26, v0
	v_lshlrev_b32_e32 v33, 16, v2
	v_rcp_f32_e32 v25, v25
	s_nop 0
	v_mul_f32_e32 v25, v27, v25
	v_add_co_u32_e64 v4, s[6:7], s65, v38
	s_nop 0
	s_nop 0
	v_addc_co_u32_e64 v5, s[6:7], 0, v39, s[6:7]
	global_load_dwordx4 v[4:7], v[4:5], off offset:512
	v_mul_f32_e32 v26, 0xbfb8aa3b, v33
	v_mul_f32_e32 v27, 0xbfb8aa3b, v32
	v_exp_f32_e32 v26, v26
	v_exp_f32_e32 v27, v27
	v_and_b32_e32 v30, 0xffff0000, v3
	v_rcp_f32_e32 v24, v24
	s_nop 0
	v_mul_f32_e32 v24, v28, v24
	v_pk_add_f32 v[26:27], v[26:27], 1.0 op_sel_hi:[1,0]
	v_and_b32_e32 v38, 0xffff0000, v2
	v_mul_f32_e32 v2, 0xbfb8aa3b, v38
	v_exp_f32_e32 v28, v2
	v_mul_f32_e32 v29, 0xbfb8aa3b, v30
	v_exp_f32_e32 v29, v29
	v_rcp_f32_e32 v3, v27
	s_nop 0
	v_mul_f32_e32 v3, v32, v3
	v_pk_add_f32 v[28:29], v[28:29], 1.0 op_sel_hi:[1,0]
	v_rcp_f32_e32 v2, v26
	s_nop 0
	v_mul_f32_e32 v2, v33, v2
	v_rcp_f32_e32 v27, v29
	s_nop 0
	v_mul_f32_e32 v27, v30, v27
	v_add_co_u32_e64 v30, s[6:7], s65, v36
	s_nop 0
	s_nop 0
	v_addc_co_u32_e64 v31, s[6:7], 0, v37, s[6:7]
	global_load_dwordx4 v[32:35], v[30:31], off offset:512
	v_rcp_f32_e32 v26, v28
	s_nop 0
	v_mul_f32_e32 v26, v38, v26
	s_barrier
	s_waitcnt vmcnt(1)
	v_lshlrev_b32_e32 v36, 16, v5
	v_lshlrev_b32_e32 v37, 16, v4
	v_mul_f32_e32 v30, 0xbfb8aa3b, v37
	v_mul_f32_e32 v31, 0xbfb8aa3b, v36
	v_exp_f32_e32 v30, v30
	v_exp_f32_e32 v31, v31
	v_and_b32_e32 v38, 0xffff0000, v5
	v_and_b32_e32 v39, 0xffff0000, v4
	v_mul_f32_e32 v4, 0xbfb8aa3b, v39
	v_pk_add_f32 v[28:29], v[30:31], 1.0 op_sel_hi:[1,0]
	v_exp_f32_e32 v30, v4
	ds_write2_b32 v47, v48, v49 offset1:16
	ds_write2_b32 v47, v50, v51 offset0:32 offset1:48
	ds_write2_b32 v47, v52, v53 offset0:68 offset1:84
	ds_write2_b32 v47, v54, v55 offset0:100 offset1:116
	ds_write2_b32 v47, v56, v57 offset0:136 offset1:152
	ds_write2_b32 v47, v58, v59 offset0:168 offset1:184
	ds_write2_b32 v47, v60, v61 offset0:204 offset1:220
	ds_write2_b32 v47, v62, v64 offset0:236 offset1:252
	v_mul_f32_e32 v31, 0xbfb8aa3b, v38
	v_exp_f32_e32 v31, v31
	v_rcp_f32_e32 v5, v29
	s_nop 0
	v_mul_f32_e32 v5, v36, v5
	v_pk_add_f32 v[30:31], v[30:31], 1.0 op_sel_hi:[1,0]
	v_rcp_f32_e32 v4, v28
	s_nop 0
	v_mul_f32_e32 v4, v37, v4
	v_rcp_f32_e32 v29, v31
	s_nop 0
	v_mul_f32_e32 v29, v38, v29
	v_lshlrev_b32_e32 v38, 16, v7
	v_lshlrev_b32_e32 v40, 16, v6
	v_mul_f32_e32 v36, 0xbfb8aa3b, v40
	v_mul_f32_e32 v37, 0xbfb8aa3b, v38
	v_exp_f32_e32 v36, v36
	v_exp_f32_e32 v37, v37
	v_rcp_f32_e32 v28, v30
	s_nop 0
	v_mul_f32_e32 v28, v39, v28
	v_and_b32_e32 v39, 0xffff0000, v7
	v_pk_add_f32 v[30:31], v[36:37], 1.0 op_sel_hi:[1,0]
	v_and_b32_e32 v41, 0xffff0000, v6
	v_mul_f32_e32 v6, 0xbfb8aa3b, v41
	v_exp_f32_e32 v36, v6
	v_mul_f32_e32 v37, 0xbfb8aa3b, v39
	v_exp_f32_e32 v37, v37
	v_rcp_f32_e32 v7, v31
	s_nop 0
	v_mul_f32_e32 v7, v38, v7
	v_pk_add_f32 v[36:37], v[36:37], 1.0 op_sel_hi:[1,0]
	v_rcp_f32_e32 v6, v30
	s_nop 0
	v_mul_f32_e32 v6, v40, v6
	v_rcp_f32_e32 v31, v37
	s_nop 0
	v_mul_f32_e32 v31, v39, v31
	s_waitcnt vmcnt(0)
	v_lshlrev_b32_e32 v42, 16, v33
	v_lshlrev_b32_e32 v43, 16, v32
	v_mul_f32_e32 v38, 0xbfb8aa3b, v43
	v_mul_f32_e32 v39, 0xbfb8aa3b, v42
	v_exp_f32_e32 v38, v38
	v_exp_f32_e32 v39, v39
	v_rcp_f32_e32 v30, v36
	s_nop 0
	v_mul_f32_e32 v30, v41, v30
	v_and_b32_e32 v68, 0xffff0000, v33
	v_pk_add_f32 v[36:37], v[38:39], 1.0 op_sel_hi:[1,0]
	v_and_b32_e32 v39, 0xffff0000, v32
	v_mul_f32_e32 v32, 0xbfb8aa3b, v39
	v_exp_f32_e32 v32, v32
	v_rcp_f32_e32 v41, v37
	s_nop 0
	v_mul_f32_e32 v41, v42, v41
	v_mul_f32_e32 v33, 0xbfb8aa3b, v68
	v_exp_f32_e32 v33, v33
	s_nop 0
	v_pk_add_f32 v[32:33], v[32:33], 1.0 op_sel_hi:[1,0]
	v_rcp_f32_e32 v40, v36
	s_nop 0
	v_mul_f32_e32 v40, v43, v40
	v_lshlrev_b32_e32 v70, 16, v34
	v_rcp_f32_e32 v43, v33
	s_nop 0
	v_mul_f32_e32 v43, v68, v43
	v_lshlrev_b32_e32 v38, 16, v35
	v_mul_f32_e32 v36, 0xbfb8aa3b, v70
	v_mul_f32_e32 v37, 0xbfb8aa3b, v38
	v_exp_f32_e32 v36, v36
	v_exp_f32_e32 v37, v37
	v_rcp_f32_e32 v42, v32
	s_nop 0
	v_mul_f32_e32 v42, v39, v42
	v_and_b32_e32 v39, 0xffff0000, v35
	v_pk_add_f32 v[32:33], v[36:37], 1.0 op_sel_hi:[1,0]
	v_and_b32_e32 v68, 0xffff0000, v34
	v_mul_f32_e32 v34, 0xbfb8aa3b, v68
	v_exp_f32_e32 v34, v34
	v_rcp_f32_e32 v71, v33
	s_nop 0
	v_mul_f32_e32 v71, v38, v71
	v_mul_f32_e32 v35, 0xbfb8aa3b, v39
	v_exp_f32_e32 v35, v35
	s_nop 0
	v_pk_add_f32 v[36:37], v[34:35], 1.0 op_sel_hi:[1,0]
	v_rcp_f32_e32 v33, v32
	s_nop 0
	v_mul_f32_e32 v70, v70, v33
	v_rcp_f32_e32 v85, v37
	s_nop 0
	v_mul_f32_e32 v85, v39, v85
	v_add_u32_e32 v32, 0x1000, v47
	ds_write2_b32 v32, v63, v65 offset0:64 offset1:80
	ds_write2_b32 v32, v67, v69 offset0:96 offset1:112
	ds_write2_b32 v32, v72, v73 offset0:132 offset1:148
	ds_write2_b32 v32, v74, v75 offset0:164 offset1:180
	ds_write2_b32 v32, v76, v77 offset0:200 offset1:216
	ds_write2_b32 v32, v78, v80 offset0:232 offset1:248
	v_add_u32_e32 v32, 0x1400, v47
	ds_write2_b32 v32, v79, v81 offset0:12 offset1:28
	ds_write2_b32 v32, v82, v83 offset0:44 offset1:60
	s_waitcnt lgkmcnt(0)
	s_barrier
; __device__ __forceinline__ unsigned pack2(float a, float b) { return (unsigned)f2bf(a) | ((unsigned)f2bf(b) << 16); }
; __device__ __forceinline__ float bflo(unsigned w) { return __uint_as_float(w << 16); }
; __device__ __forceinline__ float bfhi(unsigned w) { return __uint_as_float(w & 0xffff0000u); }
; __device__ __forceinline__ float silu_f(float g) { return g / (1.f + __expf(-g)); }
; template <int DH, int MODE>
; __device__ void attn_item(const Params& p, int layer, int b, int blk, int head, char* smem) {
;     ...
; #pragma unroll
;     for (int i = 0; i < NCH; ++i) {
;       int q = tid + 256 * i, r = q / CPR, c = (q % CPR) * 8;
;       float4 m0 = *reinterpret_cast<const float4*>(Of + r * OST + c);
;       float4 m1 = *reinterpret_cast<const float4*>(Of + r * OST + c + 4);
;       float mm[8] = {m0.x, m0.y, m0.z, m0.w, m1.x, m1.y, m1.z, m1.w};
;       unsigned gw[4] = {gt[i].x, gt[i].y, gt[i].z, gt[i].w};
;       unsigned ow[4];
; #pragma unroll
;       for (int e = 0; e < 4; ++e)
;         ow[e] = pack2(mm[2 * e] * silu_f(bflo(gw[e])), mm[2 * e + 1] * silu_f(bfhi(gw[e])));
;       *reinterpret_cast<uint4*>(Y + (tq0 + r) * YW + ycol + c) = make_uint4(ow[0], ow[1], ow[2], ow[3]);
;     }
	ds_read_b128 v[32:35], v66
	v_rcp_f32_e32 v84, v36
	s_nop 0
	v_mul_f32_e32 v84, v68, v84
	ds_read_b128 v[36:39], v66 offset:16
	v_add_co_u32_e32 v12, vcc, s70, v12
	s_waitcnt lgkmcnt(1)
	v_mov_b32_e32 v48, v32
	v_mov_b32_e32 v49, v34
	v_pk_mul_f32 v[40:41], v[40:41], v[48:49]
	v_mov_b32_e32 v34, v33
	v_pk_mul_f32 v[32:33], v[42:43], v[34:35]
	v_cvt_pk_bf16_f32 v35, 0, v40
	v_cvt_pk_bf16_f32 v34, 0, v41
	v_cvt_pk_bf16_f32 v33, 0, v33
	v_cvt_pk_bf16_f32 v32, 0, v32
	v_and_b32_e32 v33, 0xffff0000, v33
	v_and_b32_e32 v32, 0xffff0000, v32
	v_or_b32_sdwa v33, v33, v34 dst_sel:DWORD dst_unused:UNUSED_PAD src0_sel:DWORD src1_sel:WORD_1
	v_or_b32_sdwa v32, v32, v35 dst_sel:DWORD dst_unused:UNUSED_PAD src0_sel:DWORD src1_sel:WORD_1
	s_waitcnt lgkmcnt(0)
	v_mov_b32_e32 v34, v36
	v_mov_b32_e32 v35, v38
	v_pk_mul_f32 v[34:35], v[70:71], v[34:35]
	v_mov_b32_e32 v38, v37
	v_pk_mul_f32 v[36:37], v[84:85], v[38:39]
	v_cvt_pk_bf16_f32 v34, 0, v34
	v_cvt_pk_bf16_f32 v35, 0, v35
	v_cvt_pk_bf16_f32 v37, 0, v37
	v_cvt_pk_bf16_f32 v36, 0, v36
	v_and_b32_e32 v37, 0xffff0000, v37
	v_and_b32_e32 v36, 0xffff0000, v36
	v_or_b32_sdwa v35, v37, v35 dst_sel:DWORD dst_unused:UNUSED_PAD src0_sel:DWORD src1_sel:WORD_1
	v_or_b32_sdwa v34, v36, v34 dst_sel:DWORD dst_unused:UNUSED_PAD src0_sel:DWORD src1_sel:WORD_1
	ds_read_b128 v[36:39], v46
	v_addc_co_u32_e32 v13, vcc, 0, v13, vcc
	global_store_dwordx4 v[12:13], v[32:35], off offset:1024
	s_nop 0
	ds_read_b128 v[32:35], v46 offset:16
	s_waitcnt lgkmcnt(1)
	v_mov_b32_e32 v12, v36
	v_mov_b32_e32 v13, v38
	v_pk_mul_f32 v[4:5], v[4:5], v[12:13]
	v_mov_b32_e32 v38, v37
	v_pk_mul_f32 v[12:13], v[28:29], v[38:39]
	v_cvt_pk_bf16_f32 v4, 0, v4
	v_cvt_pk_bf16_f32 v5, 0, v5
	v_cvt_pk_bf16_f32 v13, 0, v13
	v_cvt_pk_bf16_f32 v12, 0, v12
	v_and_b32_e32 v13, 0xffff0000, v13
	v_and_b32_e32 v12, 0xffff0000, v12
	v_or_b32_sdwa v5, v13, v5 dst_sel:DWORD dst_unused:UNUSED_PAD src0_sel:DWORD src1_sel:WORD_1
	v_or_b32_sdwa v4, v12, v4 dst_sel:DWORD dst_unused:UNUSED_PAD src0_sel:DWORD src1_sel:WORD_1
	s_waitcnt lgkmcnt(0)
	v_mov_b32_e32 v12, v32
	v_mov_b32_e32 v13, v34
	v_pk_mul_f32 v[6:7], v[6:7], v[12:13]
	v_mov_b32_e32 v34, v33
	v_pk_mul_f32 v[12:13], v[30:31], v[34:35]
	v_cvt_pk_bf16_f32 v6, 0, v6
	v_cvt_pk_bf16_f32 v7, 0, v7
	v_cvt_pk_bf16_f32 v13, 0, v13
	v_cvt_pk_bf16_f32 v12, 0, v12
	ds_read_b128 v[28:31], v45
	v_and_b32_e32 v13, 0xffff0000, v13
	v_and_b32_e32 v12, 0xffff0000, v12
	v_add_co_u32_e32 v10, vcc, s70, v10
	v_or_b32_sdwa v7, v13, v7 dst_sel:DWORD dst_unused:UNUSED_PAD src0_sel:DWORD src1_sel:WORD_1
	v_or_b32_sdwa v6, v12, v6 dst_sel:DWORD dst_unused:UNUSED_PAD src0_sel:DWORD src1_sel:WORD_1
	v_addc_co_u32_e32 v11, vcc, 0, v11, vcc
	global_store_dwordx4 v[10:11], v[4:7], off offset:1024
	s_waitcnt lgkmcnt(0)
	v_mov_b32_e32 v10, v28
	v_mov_b32_e32 v11, v30
	ds_read_b128 v[4:7], v45 offset:16
	v_pk_mul_f32 v[0:1], v[0:1], v[10:11]
	v_mov_b32_e32 v30, v29
	v_pk_mul_f32 v[10:11], v[24:25], v[30:31]
	v_cvt_pk_bf16_f32 v0, 0, v0
	v_cvt_pk_bf16_f32 v1, 0, v1
	v_cvt_pk_bf16_f32 v11, 0, v11
	v_cvt_pk_bf16_f32 v10, 0, v10
	v_and_b32_e32 v11, 0xffff0000, v11
	v_and_b32_e32 v10, 0xffff0000, v10
	v_or_b32_sdwa v1, v11, v1 dst_sel:DWORD dst_unused:UNUSED_PAD src0_sel:DWORD src1_sel:WORD_1
	v_or_b32_sdwa v0, v10, v0 dst_sel:DWORD dst_unused:UNUSED_PAD src0_sel:DWORD src1_sel:WORD_1
	s_waitcnt lgkmcnt(0)
	v_mov_b32_e32 v10, v4
	v_mov_b32_e32 v11, v6
	v_pk_mul_f32 v[2:3], v[2:3], v[10:11]
	v_mov_b32_e32 v6, v5
	v_pk_mul_f32 v[4:5], v[26:27], v[6:7]
	v_cvt_pk_bf16_f32 v2, 0, v2
	v_cvt_pk_bf16_f32 v3, 0, v3
	v_cvt_pk_bf16_f32 v5, 0, v5
	v_cvt_pk_bf16_f32 v4, 0, v4
	v_and_b32_e32 v5, 0xffff0000, v5
	v_and_b32_e32 v4, 0xffff0000, v4
	v_or_b32_sdwa v3, v5, v3 dst_sel:DWORD dst_unused:UNUSED_PAD src0_sel:DWORD src1_sel:WORD_1
	v_or_b32_sdwa v2, v4, v2 dst_sel:DWORD dst_unused:UNUSED_PAD src0_sel:DWORD src1_sel:WORD_1
	ds_read_b128 v[4:7], v44
	v_add_co_u32_e32 v8, vcc, s70, v8
	s_nop 1
	v_addc_co_u32_e32 v9, vcc, 0, v9, vcc
	global_store_dwordx4 v[8:9], v[0:3], off offset:1024
	s_waitcnt lgkmcnt(0)
	v_mov_b32_e32 v8, v4
	v_mov_b32_e32 v9, v6
	ds_read_b128 v[0:3], v44 offset:16
	v_pk_mul_f32 v[8:9], v[16:17], v[8:9]
	v_mov_b32_e32 v6, v5
	v_pk_mul_f32 v[4:5], v[18:19], v[6:7]
	v_cvt_pk_bf16_f32 v7, 0, v8
	v_cvt_pk_bf16_f32 v6, 0, v9
	v_cvt_pk_bf16_f32 v5, 0, v5
	v_cvt_pk_bf16_f32 v4, 0, v4
	v_and_b32_e32 v5, 0xffff0000, v5
	v_and_b32_e32 v4, 0xffff0000, v4
	v_or_b32_sdwa v5, v5, v6 dst_sel:DWORD dst_unused:UNUSED_PAD src0_sel:DWORD src1_sel:WORD_1
	v_or_b32_sdwa v4, v4, v7 dst_sel:DWORD dst_unused:UNUSED_PAD src0_sel:DWORD src1_sel:WORD_1
	s_waitcnt lgkmcnt(0)
	v_mov_b32_e32 v6, v0
	v_mov_b32_e32 v7, v2
	v_pk_mul_f32 v[6:7], v[20:21], v[6:7]
	v_mov_b32_e32 v2, v1
	v_pk_mul_f32 v[0:1], v[22:23], v[2:3]
	v_cvt_pk_bf16_f32 v2, 0, v7
	v_cvt_pk_bf16_f32 v3, 0, v6
	v_cvt_pk_bf16_f32 v0, 0, v0
	v_cvt_pk_bf16_f32 v1, 0, v1
	v_and_b32_e32 v0, 0xffff0000, v0
	v_and_b32_e32 v1, 0xffff0000, v1
	v_or_b32_sdwa v6, v0, v3 dst_sel:DWORD dst_unused:UNUSED_PAD src0_sel:DWORD src1_sel:WORD_1
	v_add_co_u32_e32 v0, vcc, 0x184a1000, v14
	v_or_b32_sdwa v7, v1, v2 dst_sel:DWORD dst_unused:UNUSED_PAD src0_sel:DWORD src1_sel:WORD_1
	s_nop 0
	v_addc_co_u32_e32 v1, vcc, 0, v15, vcc
	global_store_dwordx4 v[0:1], v[4:7], off offset:1024
	s_barrier

; __device__ __forceinline__ unsigned pack2(float a, float b) { return (unsigned)f2bf(a) | ((unsigned)f2bf(b) << 16); }
; template <int DH, int MODE>
; __device__ void attn_item(const Params& p, int layer, int b, int blk, int head, char* smem) {
;     ...
; #pragma unroll 2
;         for (int c = 7; c >= 0; --c) {
;           float4 v = s4[c];
;           float e[4] = {v.x, v.y, v.z, v.w};
; #pragma unroll
;           for (int k = 3; k >= 0; --k) {
;             float z = e[k];
;             bool valid = (kpb + c * 4 + k) < qpos;
;             float sp = fmaxf(z, 0.f) + __builtin_amdgcn_logf(1.f + __builtin_amdgcn_exp2f(-fabsf(z)));
;             run += valid ? -sp : 0.f;
;             e[k] = z + run;
;           }
;           s4[c] = make_float4(e[0], e[1], e[2], e[3]);
;         }
;         float other = __shfl_xor(run, 1);
;         float offs = m_run + (half == 0 ? other : 0.f);
; #pragma unroll 2
;         for (int s8 = 0; s8 < 4; ++s8) {
;           float4 va = s4[2 * s8], vb = s4[2 * s8 + 1];
;           float e[8] = {va.x, va.y, va.z, va.w, vb.x, vb.y, vb.z, vb.w};
;           float pv[8];
; #pragma unroll
;           for (int k = 0; k < 8; ++k) {
;             bool valid = (kpb + s8 * 8 + k) < qpos;
;             pv[k] = valid ? __builtin_amdgcn_exp2f(e[k] + offs) : 0.f;
;           }
;           uint4 ov;
;           ov.x = pack2(pv[0], pv[1]); ov.y = pack2(pv[2], pv[3]);
;           ov.z = pack2(pv[4], pv[5]); ov.w = pack2(pv[6], pv[7]);
;           *reinterpret_cast<uint4*>(prow + s8 * 16) = ov;
;         }
.LBB0_1168:
	ds_read_b128 v[150:153], v148 offset:16
	ds_read_b128 v[176:179], v148
	v_add_u32_e32 v149, s46, v173
	v_add_u32_e32 v182, 0x3fdd, v149
	v_cmp_lt_i32_e32 vcc, v182, v144
	s_waitcnt lgkmcnt(1)
	v_exp_f32_e64 v175, -|v151|
	v_exp_f32_e64 v184, -|v150|
	v_max_f32_e32 v183, 0, v151
	v_add_f32_e32 v175, 1.0, v175
	v_log_f32_e32 v175, v175
	v_add_f32_e32 v182, 1.0, v184
	v_exp_f32_e64 v184, -|v153|
	v_add_u32_e32 v147, 0x3fdc, v149
	v_add_f32_e32 v175, v183, v175
	v_log_f32_e32 v182, v182
	v_cndmask_b32_e64 v175, 0, -v175, vcc
	v_cmp_lt_i32_e32 vcc, v147, v144
	v_add_f32_e32 v147, 1.0, v184
	v_exp_f32_e64 v184, -|v152|
	v_log_f32_e32 v147, v147
	v_max_f32_e32 v183, 0, v150
	v_add_u32_e32 v180, 0x3fdf, v149
	v_add_f32_e32 v182, v183, v182
	v_cndmask_b32_e64 v182, 0, -v182, vcc
	v_max_f32_e32 v183, 0, v153
	v_cmp_lt_i32_e32 vcc, v180, v144
	v_add_f32_e32 v180, 1.0, v184
	v_add_f32_e32 v147, v183, v147
	v_log_f32_e32 v180, v180
	v_cndmask_b32_e64 v147, 0, -v147, vcc
	v_add_f32_e32 v147, v146, v147
	v_add_u32_e32 v181, 0x3fde, v149
	v_max_f32_e32 v146, 0, v152
	v_add_f32_e32 v146, v146, v180
	v_cmp_lt_i32_e32 vcc, v181, v144
	s_add_i32 s46, s46, -8
	s_cmpk_eq_i32 s46, 0xffe0
	v_cndmask_b32_e64 v146, 0, -v146, vcc
	v_add_f32_e32 v146, v146, v147
	v_pk_add_f32 v[152:153], v[152:153], v[146:147]
	v_add_f32_e32 v147, v175, v146
	v_add_f32_e32 v146, v182, v147
	v_pk_add_f32 v[150:151], v[150:151], v[146:147]
	ds_write_b128 v148, v[150:153] offset:16
	s_waitcnt lgkmcnt(1)
	v_exp_f32_e64 v150, -|v177|
	v_exp_f32_e64 v175, -|v176|
	v_add_u32_e32 v147, 0x3fd8, v149
	v_add_f32_e32 v150, 1.0, v150
	v_log_f32_e32 v150, v150
	v_add_u32_e32 v151, 0x3fdb, v149
	v_add_u32_e32 v152, 0x3fda, v149
	v_add_u32_e32 v149, 0x3fd9, v149
	v_max_f32_e32 v153, 0, v177
	v_add_f32_e32 v150, v153, v150
	v_cmp_lt_i32_e32 vcc, v149, v144
	v_max_f32_e32 v153, 0, v176
	s_nop 0
	v_cndmask_b32_e64 v149, 0, -v150, vcc
	v_add_f32_e32 v150, 1.0, v175
	v_exp_f32_e64 v175, -|v179|
	v_log_f32_e32 v150, v150
	v_cmp_lt_i32_e32 vcc, v147, v144
	v_add_f32_e32 v147, 1.0, v175
	v_exp_f32_e64 v175, -|v178|
	v_log_f32_e32 v147, v147
	v_add_f32_e32 v150, v153, v150
	v_cndmask_b32_e64 v150, 0, -v150, vcc
	v_max_f32_e32 v153, 0, v179
	v_cmp_lt_i32_e32 vcc, v151, v144
	v_add_f32_e32 v151, 1.0, v175
	v_add_f32_e32 v147, v153, v147
	v_log_f32_e32 v151, v151
	v_cndmask_b32_e64 v147, 0, -v147, vcc
	v_add_f32_e32 v147, v146, v147
	v_max_f32_e32 v146, 0, v178
	v_add_f32_e32 v146, v146, v151
	v_cmp_lt_i32_e32 vcc, v152, v144
	s_nop 1
	v_cndmask_b32_e64 v146, 0, -v146, vcc
	v_add_f32_e32 v146, v146, v147
	v_pk_add_f32 v[152:153], v[178:179], v[146:147]
	v_add_f32_e32 v147, v149, v146
	v_add_f32_e32 v146, v150, v147
	v_pk_add_f32 v[150:151], v[176:177], v[146:147]
	ds_write_b128 v148, v[150:153]
	v_subrev_u32_e32 v148, 32, v148
	s_cbranch_scc0 .LBB0_1168
	ds_bpermute_b32 v147, v163, v146
	s_mov_b32 s81, 0
	v_mov_b32_e32 v175, v168
	v_mov_b32_e32 v177, v167
	s_waitcnt lgkmcnt(0)
	v_cndmask_b32_e64 v148, 0, v147, s[8:9]
	v_add_f32_e32 v176, v174, v148
	s_branch .LBB0_1171
.LBB0_1170:
	s_or_b64 exec, exec, s[46:47]
	s_waitcnt lgkmcnt(3)
	v_add_f32_e32 v152, v176, v152
	v_exp_f32_e32 v152, v152
	s_waitcnt lgkmcnt(1)
	v_add_f32_e32 v149, v176, v149
	v_exp_f32_e32 v149, v149
	v_add_u32_e32 v182, 0x3fc9, v178
	v_add_f32_e32 v151, v176, v151
	v_add_f32_e32 v148, v176, v148
	v_cmp_lt_i32_e32 vcc, v182, v144
	v_exp_f32_e32 v185, v151
	v_exp_f32_e32 v186, v148
	v_add_u32_e32 v148, 0x3fce, v178
	s_waitcnt lgkmcnt(0)
	v_add_f32_e32 v151, v176, v180
	v_cndmask_b32_e32 v152, 0, v152, vcc
	v_exp_f32_e32 v151, v151
	v_cmp_lt_i32_e32 vcc, v148, v144
	v_add_u32_e32 v148, 0x3fcf, v178
	v_add_f32_e32 v153, v176, v153
	v_cndmask_b32_e32 v149, 0, v149, vcc
	v_cmp_lt_i32_e32 vcc, v148, v144
	v_cvt_pk_bf16_f32 v148, 0, v179
	v_exp_f32_e32 v153, v153
	v_lshrrev_b32_e32 v148, 16, v148
	v_cvt_pk_bf16_f32 v152, 0, v152
	v_add_f32_e32 v150, v176, v150
	v_cndmask_b32_e32 v151, 0, v151, vcc
	v_and_or_b32 v148, v152, s41, v148
	v_or_b32_e32 v182, 2, v181
	v_exp_f32_e32 v150, v150
	v_cvt_pk_bf16_f32 v149, 0, v149
	v_or_b32_e32 v183, 4, v181
	v_lshrrev_b32_e32 v149, 16, v149
	v_cvt_pk_bf16_f32 v151, 0, v151
	v_cmp_lt_i32_e32 vcc, v182, v144
	v_or_b32_e32 v184, 5, v181
	v_or_b32_e32 v181, 3, v181
	v_and_or_b32 v151, v151, s41, v149
	v_cndmask_b32_e32 v149, 0, v153, vcc
	v_cmp_lt_i32_e32 vcc, v183, v131
	v_cvt_pk_bf16_f32 v149, 0, v149
	s_nop 0
	v_cndmask_b32_e32 v152, 0, v185, vcc
	v_cmp_lt_i32_e32 vcc, v181, v144
	v_cvt_pk_bf16_f32 v152, 0, v152
	s_nop 0
	v_cndmask_b32_e32 v150, 0, v150, vcc
	v_cmp_lt_i32_e32 vcc, v184, v131
	v_cvt_pk_bf16_f32 v150, 0, v150
	s_nop 0
	v_cndmask_b32_e32 v153, 0, v186, vcc
	v_cvt_pk_bf16_f32 v153, 0, v153
	v_and_b32_e32 v153, 0xffff0000, v153
	v_and_b32_e32 v178, 0xffff0000, v150
	v_or_b32_sdwa v150, v153, v152 dst_sel:DWORD dst_unused:UNUSED_PAD src0_sel:DWORD src1_sel:WORD_1
	v_or_b32_sdwa v149, v178, v149 dst_sel:DWORD dst_unused:UNUSED_PAD src0_sel:DWORD src1_sel:WORD_1
	s_add_i32 s81, s81, 16
	ds_write_b128 v175, v[148:151] offset:16
	v_add_u32_e32 v177, 64, v177
	s_cmp_eq_u32 s81, 32
	v_add_u32_e32 v175, 32, v175
	s_cbranch_scc1 .LBB0_1176

; __device__ __forceinline__ unsigned pack2(float a, float b) { return (unsigned)f2bf(a) | ((unsigned)f2bf(b) << 16); }
; template <int DH, int MODE>
; __device__ void attn_item(const Params& p, int layer, int b, int blk, int head, char* smem) {
;     ...
;         for (int s8 = 0; s8 < 4; ++s8) {
;           float4 va = s4[2 * s8], vb = s4[2 * s8 + 1];
;           float e[8] = {va.x, va.y, va.z, va.w, vb.x, vb.y, vb.z, vb.w};
;           float pv[8];
; #pragma unroll
;           for (int k = 0; k < 8; ++k) {
;             bool valid = (kpb + s8 * 8 + k) < qpos;
;             pv[k] = valid ? __builtin_amdgcn_exp2f(e[k] + offs) : 0.f;
;           }
;           uint4 ov;
;           ov.x = pack2(pv[0], pv[1]); ov.y = pack2(pv[2], pv[3]);
;           ov.z = pack2(pv[4], pv[5]); ov.w = pack2(pv[6], pv[7]);
;           *reinterpret_cast<uint4*>(prow + s8 * 16) = ov;
;         }
.LBB0_1173:
	s_or_b64 exec, exec, s[46:47]
	s_waitcnt lgkmcnt(3)
	v_add_f32_e32 v152, v176, v152
	v_exp_f32_e32 v152, v152
	s_waitcnt lgkmcnt(1)
	v_add_f32_e32 v149, v176, v149
	v_exp_f32_e32 v149, v149
	v_add_u32_e32 v183, 0x3fc1, v178
	v_add_f32_e32 v151, v176, v151
	v_add_f32_e32 v148, v176, v148
	v_cmp_lt_i32_e32 vcc, v183, v144
	v_exp_f32_e32 v186, v151
	v_exp_f32_e32 v187, v148
	v_add_u32_e32 v148, 0x3fc6, v178
	s_waitcnt lgkmcnt(0)
	v_add_f32_e32 v151, v176, v180
	v_cndmask_b32_e32 v152, 0, v152, vcc
	v_exp_f32_e32 v151, v151
	v_cmp_lt_i32_e32 vcc, v148, v144
	v_add_u32_e32 v148, 0x3fc7, v178
	v_add_f32_e32 v153, v176, v153
	v_cndmask_b32_e32 v149, 0, v149, vcc
	v_cmp_lt_i32_e32 vcc, v148, v144
	v_cvt_pk_bf16_f32 v148, 0, v181
	v_exp_f32_e32 v153, v153
	v_lshrrev_b32_e32 v148, 16, v148
	v_cvt_pk_bf16_f32 v152, 0, v152
	v_add_f32_e32 v150, v176, v150
	v_cndmask_b32_e32 v151, 0, v151, vcc
	v_and_or_b32 v148, v152, s41, v148
	v_or_b32_e32 v183, 2, v182
	v_exp_f32_e32 v150, v150
	v_cvt_pk_bf16_f32 v149, 0, v149
	v_or_b32_e32 v184, 4, v182
	v_lshrrev_b32_e32 v149, 16, v149
	v_cvt_pk_bf16_f32 v151, 0, v151
	v_cmp_lt_i32_e32 vcc, v183, v144
	v_or_b32_e32 v185, 5, v182
	v_or_b32_e32 v182, 3, v182
	v_and_or_b32 v151, v151, s41, v149
	v_cndmask_b32_e32 v149, 0, v153, vcc
	v_cmp_lt_i32_e32 vcc, v184, v131
	v_cvt_pk_bf16_f32 v149, 0, v149
	s_nop 0
	v_cndmask_b32_e32 v152, 0, v186, vcc
	v_cmp_lt_i32_e32 vcc, v182, v144
	v_cvt_pk_bf16_f32 v152, 0, v152
	s_nop 0
	v_cndmask_b32_e32 v150, 0, v150, vcc
	v_cmp_lt_i32_e32 vcc, v185, v131
	v_cvt_pk_bf16_f32 v150, 0, v150
	s_nop 0
	v_cndmask_b32_e32 v153, 0, v187, vcc
	v_cvt_pk_bf16_f32 v153, 0, v153
	v_and_b32_e32 v153, 0xffff0000, v153
	v_and_b32_e32 v180, 0xffff0000, v150
	v_or_b32_sdwa v150, v153, v152 dst_sel:DWORD dst_unused:UNUSED_PAD src0_sel:DWORD src1_sel:WORD_1
	v_or_b32_sdwa v149, v180, v149 dst_sel:DWORD dst_unused:UNUSED_PAD src0_sel:DWORD src1_sel:WORD_1
	ds_write_b128 v175, v[148:151]
	ds_read2_b32 v[152:153], v177 offset0:9 offset1:10
	ds_read2_b32 v[150:151], v177 offset0:11 offset1:12
	ds_read2_b32 v[148:149], v177 offset0:13 offset1:14
	ds_read_b32 v180, v177 offset:60
	v_add_u32_e32 v181, 0x3fc8, v178
	v_cmp_lt_i32_e32 vcc, v181, v144
	s_and_saveexec_b64 s[46:47], vcc
	s_cbranch_execz .LBB0_1170
	ds_read_b32 v179, v177 offset:32
	s_waitcnt lgkmcnt(0)
	v_add_f32_e32 v179, v176, v179
	v_exp_f32_e32 v179, v179
	s_branch .LBB0_1170

; template <int WM, int WN>
; __device__ __forceinline__ void store_tile_bf16(const f32x4 (&acc)[WM][WN], u16* dst, int ld, char* smem) {
;   constexpr int BM = 32 * WM, BN = 32 * WN, STR = BN + 8;
;   const int tid = opaque_tid(), lane = tid & 63, wid = tid >> 6;
;   const int wr = wid >> 1, wc = wid & 1, fr = lane & 15, fq = lane >> 4;
;   u16* T = reinterpret_cast<u16*>(smem);
; #pragma unroll
;   for (int m = 0; m < WM; ++m)
; #pragma unroll
;     for (int n = 0; n < WN; ++n)
; #pragma unroll
;       for (int j = 0; j < 4; ++j)
;         T[(wr * 16 * WM + m * 16 + fq * 4 + j) * STR + wc * 16 * WN + n * 16 + fr] = f2bf(acc[m][n][j]);
;   __syncthreads();
.LBB0_1220:
	v_mov_b32_e32 v1, v232
	s_waitcnt vmcnt(7)
	v_lshrrev_b32_e32 v3, 2, v1
	v_lshrrev_b32_e32 v2, 1, v1
	v_and_b32_e32 v3, 12, v3
	v_and_or_b32 v2, v2, s50, v3
	v_and_b32_e32 v3, 0x4f, v1
	v_mul_lo_u32 v2, v2, s51
	v_lshl_add_u32 v2, v3, 1, v2
	v_cvt_pk_bf16_f32 v3, 0, v65
	ds_write_b16_d16_hi v2, v3 offset:272
	v_cvt_pk_bf16_f32 v3, 0, v66
	ds_write_b16_d16_hi v2, v3 offset:544
	v_cvt_pk_bf16_f32 v3, 0, v67
	ds_write_b16_d16_hi v2, v3 offset:816
	v_cvt_pk_bf16_f32 v3, 0, v60
	ds_write_b16_d16_hi v2, v3 offset:32
	v_cvt_pk_bf16_f32 v3, 0, v61
	ds_write_b16_d16_hi v2, v3 offset:304
	v_cvt_pk_bf16_f32 v3, 0, v62
	ds_write_b16_d16_hi v2, v3 offset:576
	v_cvt_pk_bf16_f32 v3, 0, v63
	ds_write_b16_d16_hi v2, v3 offset:848
	v_cvt_pk_bf16_f32 v3, 0, v56
	ds_write_b16_d16_hi v2, v3 offset:64
	v_cvt_pk_bf16_f32 v3, 0, v57
	ds_write_b16_d16_hi v2, v3 offset:336
	v_cvt_pk_bf16_f32 v3, 0, v58
	ds_write_b16_d16_hi v2, v3 offset:608
	v_cvt_pk_bf16_f32 v3, 0, v59
	ds_write_b16_d16_hi v2, v3 offset:880
	v_cvt_pk_bf16_f32 v3, 0, v52
	ds_write_b16_d16_hi v2, v3 offset:96
	v_cvt_pk_bf16_f32 v3, 0, v53
	ds_write_b16_d16_hi v2, v3 offset:368
	v_cvt_pk_bf16_f32 v3, 0, v54
	ds_write_b16_d16_hi v2, v3 offset:640
	v_cvt_pk_bf16_f32 v3, 0, v55
	ds_write_b16_d16_hi v2, v3 offset:912
	v_cvt_pk_bf16_f32 v3, 0, v48
	ds_write_b16_d16_hi v2, v3 offset:4352
	v_cvt_pk_bf16_f32 v3, 0, v49
	ds_write_b16_d16_hi v2, v3 offset:4624
	v_cvt_pk_bf16_f32 v3, 0, v50
	ds_write_b16_d16_hi v2, v3 offset:4896
	v_cvt_pk_bf16_f32 v3, 0, v51
	ds_write_b16_d16_hi v2, v3 offset:5168
	v_cvt_pk_bf16_f32 v3, 0, v44
	ds_write_b16_d16_hi v2, v3 offset:4384
	v_cvt_pk_bf16_f32 v3, 0, v45
	ds_write_b16_d16_hi v2, v3 offset:4656
	v_cvt_pk_bf16_f32 v3, 0, v46
	ds_write_b16_d16_hi v2, v3 offset:4928
	v_cvt_pk_bf16_f32 v3, 0, v47
	ds_write_b16_d16_hi v2, v3 offset:5200
	v_cvt_pk_bf16_f32 v3, 0, v40
	ds_write_b16_d16_hi v2, v3 offset:4416
	v_cvt_pk_bf16_f32 v3, 0, v41
	ds_write_b16_d16_hi v2, v3 offset:4688
	v_cvt_pk_bf16_f32 v3, 0, v42
	ds_write_b16_d16_hi v2, v3 offset:4960
	v_cvt_pk_bf16_f32 v3, 0, v43
	ds_write_b16_d16_hi v2, v3 offset:5232
	v_cvt_pk_bf16_f32 v3, 0, v36
	ds_write_b16_d16_hi v2, v3 offset:4448
	v_cvt_pk_bf16_f32 v3, 0, v37
	ds_write_b16_d16_hi v2, v3 offset:4720
	v_cvt_pk_bf16_f32 v3, 0, v38
	ds_write_b16_d16_hi v2, v3 offset:4992
	v_cvt_pk_bf16_f32 v3, 0, v39
	ds_write_b16_d16_hi v2, v3 offset:5264
	v_cvt_pk_bf16_f32 v3, 0, v32
	ds_write_b16_d16_hi v2, v3 offset:8704
	v_cvt_pk_bf16_f32 v3, 0, v33
	ds_write_b16_d16_hi v2, v3 offset:8976
	v_cvt_pk_bf16_f32 v3, 0, v34
	ds_write_b16_d16_hi v2, v3 offset:9248
	v_cvt_pk_bf16_f32 v3, 0, v35
	ds_write_b16_d16_hi v2, v3 offset:9520
	v_cvt_pk_bf16_f32 v3, 0, v28
	ds_write_b16_d16_hi v2, v3 offset:8736
	v_cvt_pk_bf16_f32 v3, 0, v29
	ds_write_b16_d16_hi v2, v3 offset:9008
	v_cvt_pk_bf16_f32 v3, 0, v30
	ds_write_b16_d16_hi v2, v3 offset:9280
	v_cvt_pk_bf16_f32 v3, 0, v31
	ds_write_b16_d16_hi v2, v3 offset:9552
	v_cvt_pk_bf16_f32 v3, 0, v24
	ds_write_b16_d16_hi v2, v3 offset:8768
	v_cvt_pk_bf16_f32 v3, 0, v25
	ds_write_b16_d16_hi v2, v3 offset:9040
	v_cvt_pk_bf16_f32 v3, 0, v26
	ds_write_b16_d16_hi v2, v3 offset:9312
	v_cvt_pk_bf16_f32 v3, 0, v27
	ds_write_b16_d16_hi v2, v3 offset:9584
	v_cvt_pk_bf16_f32 v3, 0, v20
	ds_write_b16_d16_hi v2, v3 offset:8800
	v_cvt_pk_bf16_f32 v3, 0, v21
	ds_write_b16_d16_hi v2, v3 offset:9072
	v_cvt_pk_bf16_f32 v3, 0, v22
	ds_write_b16_d16_hi v2, v3 offset:9344
	v_cvt_pk_bf16_f32 v3, 0, v23
	ds_write_b16_d16_hi v2, v3 offset:9616
	v_cvt_pk_bf16_f32 v3, 0, v16
	ds_write_b16_d16_hi v2, v3 offset:13056
	v_cvt_pk_bf16_f32 v3, 0, v17
	ds_write_b16_d16_hi v2, v3 offset:13328
	v_cvt_pk_bf16_f32 v3, 0, v18
	ds_write_b16_d16_hi v2, v3 offset:13600
	v_cvt_pk_bf16_f32 v3, 0, v19
	ds_write_b16_d16_hi v2, v3 offset:13872
	v_cvt_pk_bf16_f32 v3, 0, v12
	ds_write_b16_d16_hi v2, v3 offset:13088
	v_cvt_pk_bf16_f32 v3, 0, v13
	ds_write_b16_d16_hi v2, v3 offset:13360
	v_cvt_pk_bf16_f32 v3, 0, v14
	ds_write_b16_d16_hi v2, v3 offset:13632
	v_cvt_pk_bf16_f32 v3, 0, v15
	ds_write_b16_d16_hi v2, v3 offset:13904
	v_cvt_pk_bf16_f32 v3, 0, v8
	ds_write_b16_d16_hi v2, v3 offset:13120
	v_cvt_pk_bf16_f32 v3, 0, v9
	ds_write_b16_d16_hi v2, v3 offset:13392
	v_cvt_pk_bf16_f32 v3, 0, v10
	ds_write_b16_d16_hi v2, v3 offset:13664
	v_cvt_pk_bf16_f32 v3, 0, v11
	ds_write_b16_d16_hi v2, v3 offset:13936
	v_cvt_pk_bf16_f32 v3, 0, v4
	ds_write_b16_d16_hi v2, v3 offset:13152
	v_cvt_pk_bf16_f32 v3, 0, v5
	ds_write_b16_d16_hi v2, v3 offset:13424
	v_cvt_pk_bf16_f32 v3, 0, v6
	ds_write_b16_d16_hi v2, v3 offset:13696
	v_cvt_pk_bf16_f32 v64, 0, v64
	v_cvt_pk_bf16_f32 v3, 0, v7
	ds_write_b16_d16_hi v2, v64
	ds_write_b16_d16_hi v2, v3 offset:13968
	v_ashrrev_i32_e32 v2, 31, v1
	s_lshl_b64 s[6:7], s[16:17], 1
	v_lshrrev_b32_e32 v2, 28, v2
	s_add_u32 s8, s44, s6
	v_add_u32_e32 v2, v1, v2
	s_addc_u32 s9, s45, s7
	s_lshl_b64 s[6:7], s[22:23], 1
	v_ashrrev_i32_e32 v6, 4, v2
	v_and_b32_e32 v2, -16, v2
	s_add_u32 s6, s8, s6
	v_sub_u32_e32 v2, v1, v2
	v_ashrrev_i32_e32 v7, 31, v6
	s_addc_u32 s7, s9, s7
	v_mul_lo_u32 v3, v6, s51
	v_lshlrev_b32_e32 v8, 3, v2
	v_lshlrev_b64 v[6:7], 11, v[6:7]
	v_ashrrev_i32_e32 v9, 31, v8
	v_lshl_add_u64 v[6:7], s[6:7], 0, v[6:7]
	v_lshl_add_u64 v[10:11], v[8:9], 1, v[6:7]
	v_add_u32_e32 v6, 0x100, v1
	v_ashrrev_i32_e32 v7, 31, v6
	v_lshl_add_u32 v2, v2, 4, v3
	v_lshrrev_b32_e32 v7, 28, v7
	s_waitcnt lgkmcnt(0)
	s_barrier
; template <int WM, int WN>
; __device__ __forceinline__ void store_tile_bf16(const f32x4 (&acc)[WM][WN], u16* dst, int ld, char* smem) {
;     ...
;   constexpr int CPR = BN / 8;
; #pragma unroll
;   for (int i = 0; i < BM * CPR / 256; ++i) {
;     int q = tid + 256 * i, row = q / CPR, c = q % CPR;
;     uint4 v = *reinterpret_cast<const uint4*>(T + row * STR + c * 8);
;     *reinterpret_cast<uint4*>(dst + (size_t)row * ld + c * 8) = v;
;   }
	ds_read_b128 v[2:5], v2
	v_add_u32_e32 v7, v6, v7
	v_ashrrev_i32_e32 v12, 4, v7
	v_and_b32_e32 v7, -16, v7
	v_sub_u32_e32 v13, v6, v7
	v_mul_lo_u32 v6, v12, s51
	v_lshl_add_u32 v6, v13, 4, v6
	ds_read_b128 v[6:9], v6
	s_waitcnt lgkmcnt(1)
	global_store_dwordx4 v[10:11], v[2:5], off
	s_add_i32 s52, s52, s61
	s_cmp_lt_i32 s52, s62
	v_lshlrev_b32_e32 v2, 3, v13
	v_ashrrev_i32_e32 v13, 31, v12
	v_lshlrev_b64 v[4:5], 11, v[12:13]
	v_ashrrev_i32_e32 v3, 31, v2
	v_lshl_add_u64 v[4:5], s[6:7], 0, v[4:5]
	v_lshl_add_u64 v[2:3], v[2:3], 1, v[4:5]
	s_waitcnt lgkmcnt(0)
	global_store_dwordx4 v[2:3], v[6:9], off
	v_add_u32_e32 v2, 0x200, v1
	v_ashrrev_i32_e32 v3, 31, v2
	v_lshrrev_b32_e32 v3, 28, v3
	v_add_u32_e32 v3, v2, v3
	v_ashrrev_i32_e32 v6, 4, v3
	v_and_b32_e32 v3, -16, v3
	v_sub_u32_e32 v2, v2, v3
	v_ashrrev_i32_e32 v7, 31, v6
	v_mul_lo_u32 v3, v6, s51
	v_lshlrev_b32_e32 v8, 3, v2
	v_lshlrev_b64 v[6:7], 11, v[6:7]
	v_ashrrev_i32_e32 v9, 31, v8
	v_lshl_add_u64 v[6:7], s[6:7], 0, v[6:7]
	v_lshl_add_u64 v[10:11], v[8:9], 1, v[6:7]
	v_add_u32_e32 v6, 0x300, v1
	v_ashrrev_i32_e32 v7, 31, v6
	v_lshl_add_u32 v2, v2, 4, v3
	v_lshrrev_b32_e32 v7, 28, v7
	ds_read_b128 v[2:5], v2
	v_add_u32_e32 v7, v6, v7
	v_ashrrev_i32_e32 v12, 4, v7
	v_and_b32_e32 v7, -16, v7
	v_sub_u32_e32 v13, v6, v7
	v_mul_lo_u32 v6, v12, s51
	v_lshl_add_u32 v6, v13, 4, v6
	ds_read_b128 v[6:9], v6
	s_waitcnt lgkmcnt(1)
	global_store_dwordx4 v[10:11], v[2:5], off
	s_nop 1
	v_lshlrev_b32_e32 v2, 3, v13
	v_ashrrev_i32_e32 v13, 31, v12
	v_lshlrev_b64 v[4:5], 11, v[12:13]
	v_ashrrev_i32_e32 v3, 31, v2
	v_lshl_add_u64 v[4:5], s[6:7], 0, v[4:5]
	v_lshl_add_u64 v[2:3], v[2:3], 1, v[4:5]
	s_waitcnt lgkmcnt(0)
	global_store_dwordx4 v[2:3], v[6:9], off
	v_add_u32_e32 v2, 0x400, v1
	v_ashrrev_i32_e32 v3, 31, v2
	v_lshrrev_b32_e32 v3, 28, v3
	v_add_u32_e32 v3, v2, v3
	v_ashrrev_i32_e32 v6, 4, v3
	v_and_b32_e32 v3, -16, v3
	v_sub_u32_e32 v2, v2, v3
	v_ashrrev_i32_e32 v7, 31, v6
	v_mul_lo_u32 v3, v6, s51
	v_lshlrev_b32_e32 v8, 3, v2
	v_lshlrev_b64 v[6:7], 11, v[6:7]
	v_ashrrev_i32_e32 v9, 31, v8
	v_lshl_add_u64 v[6:7], s[6:7], 0, v[6:7]
	v_lshl_add_u64 v[10:11], v[8:9], 1, v[6:7]
	v_add_u32_e32 v6, 0x500, v1
	v_ashrrev_i32_e32 v7, 31, v6
	v_lshl_add_u32 v2, v2, 4, v3
	v_lshrrev_b32_e32 v7, 28, v7
	ds_read_b128 v[2:5], v2
	v_add_u32_e32 v7, v6, v7
	v_ashrrev_i32_e32 v12, 4, v7
	v_and_b32_e32 v7, -16, v7
	v_sub_u32_e32 v13, v6, v7
	v_mul_lo_u32 v6, v12, s51
	v_lshl_add_u32 v6, v13, 4, v6
	ds_read_b128 v[6:9], v6
	s_waitcnt lgkmcnt(1)
	global_store_dwordx4 v[10:11], v[2:5], off
	s_nop 1
	v_lshlrev_b32_e32 v2, 3, v13
	v_ashrrev_i32_e32 v13, 31, v12
	v_lshlrev_b64 v[4:5], 11, v[12:13]
	v_ashrrev_i32_e32 v3, 31, v2
	v_lshl_add_u64 v[4:5], s[6:7], 0, v[4:5]
	v_lshl_add_u64 v[2:3], v[2:3], 1, v[4:5]
	s_waitcnt lgkmcnt(0)
	global_store_dwordx4 v[2:3], v[6:9], off
	v_add_u32_e32 v2, 0x600, v1
	v_ashrrev_i32_e32 v3, 31, v2
	v_lshrrev_b32_e32 v3, 28, v3
	v_add_u32_e32 v3, v2, v3
	v_ashrrev_i32_e32 v6, 4, v3
	v_and_b32_e32 v3, -16, v3
	v_sub_u32_e32 v2, v2, v3
	v_ashrrev_i32_e32 v7, 31, v6
	v_mul_lo_u32 v3, v6, s51
	v_lshlrev_b32_e32 v8, 3, v2
	v_lshlrev_b64 v[6:7], 11, v[6:7]
	v_ashrrev_i32_e32 v9, 31, v8
	v_lshl_add_u64 v[6:7], s[6:7], 0, v[6:7]
	v_add_u32_e32 v1, 0x700, v1
	v_lshl_add_u64 v[10:11], v[8:9], 1, v[6:7]
	v_ashrrev_i32_e32 v6, 31, v1
	v_lshrrev_b32_e32 v6, 28, v6
	v_lshl_add_u32 v2, v2, 4, v3
	v_add_u32_e32 v6, v1, v6
	ds_read_b128 v[2:5], v2
	v_ashrrev_i32_e32 v12, 4, v6
	v_and_b32_e32 v6, -16, v6
	v_sub_u32_e32 v1, v1, v6
	v_mul_lo_u32 v6, v12, s51
	v_lshl_add_u32 v6, v1, 4, v6
	ds_read_b128 v[6:9], v6
	v_ashrrev_i32_e32 v13, 31, v12
	s_waitcnt lgkmcnt(1)
	global_store_dwordx4 v[10:11], v[2:5], off
	s_nop 1
	v_lshlrev_b32_e32 v2, 3, v1
	v_lshlrev_b64 v[4:5], 11, v[12:13]
	v_ashrrev_i32_e32 v3, 31, v2
	v_lshl_add_u64 v[4:5], s[6:7], 0, v[4:5]
	v_lshl_add_u64 v[2:3], v[2:3], 1, v[4:5]
	s_waitcnt lgkmcnt(0)
	global_store_dwordx4 v[2:3], v[6:9], off
	s_cbranch_scc0 .LBB0_1241

; __device__ void phase_merge(const Params& p, int layer, char* smem) {
;     ...
;         [&](int s) {
;           int seg = s / 48, r = s - seg * 48;
;           if (r == 31) {
; #pragma unroll
;             for (int n = 0; n < 4; ++n) {
;               float bm = bmp[seg * 1024 + n * 16];
; #pragma unroll
;               for (int m = 0; m < 4; ++m)
; #pragma unroll
;                 for (int j = 0; j < 4; ++j) {
;                   GL[((m * 4 + n) * 4 + j) * 256] = f2bf(1.f / (1.f + __expf(-(acc[m][n][j] + bm))));
;                   acc[m][n][j] = 0.f;
;                 }
;             }
.LBB0_1237:
	s_cmp_eq_u32 s10, 31
	s_cbranch_scc0 .LBB0_1239
	s_mul_i32 s6, s54, 0xab
	s_lshr_b32 s6, s6, 1
	s_and_b32 s14, s6, 0x7000
	v_lshl_add_u64 v[2:3], v[230:231], 0, s[14:15]
	global_load_dword v164, v[2:3], off
	global_load_dword v165, v[2:3], off offset:64
	global_load_dword v166, v[2:3], off offset:128
	global_load_dword v1, v[2:3], off offset:192
	s_waitcnt vmcnt(3)
	v_add_f32_e32 v2, v160, v164
	v_add_f32_e32 v3, v161, v164
	v_mul_f32_e32 v2, 0xbfb8aa3b, v2
	v_add_f32_e32 v167, v162, v164
	v_mul_f32_e32 v3, 0xbfb8aa3b, v3
	v_exp_f32_e32 v2, v2
	v_add_f32_e32 v168, v163, v164
	v_mul_f32_e32 v167, 0xbfb8aa3b, v167
	v_exp_f32_e32 v3, v3
	v_mul_f32_e32 v168, 0xbfb8aa3b, v168
	v_exp_f32_e32 v167, v167
	v_exp_f32_e32 v168, v168
	v_add_f32_e32 v2, 1.0, v2
	v_add_f32_e32 v3, 1.0, v3
	v_add_f32_e32 v169, v144, v164
	v_add_f32_e32 v167, 1.0, v167
	v_mul_f32_e32 v169, 0xbfb8aa3b, v169
	v_add_f32_e32 v168, 1.0, v168
	v_exp_f32_e32 v169, v169
	s_nop 0
	v_add_f32_e32 v169, 1.0, v169
	v_div_scale_f32 v174, s[6:7], 1.0, v3, 1.0
	v_div_scale_f32 v176, s[8:9], 1.0, v167, 1.0
	v_div_scale_f32 v178, s[10:11], 1.0, v168, 1.0
	v_add_f32_e32 v170, v145, v164
	s_mov_b64 vcc, s[6:7]
	v_mul_f32_e32 v170, 0xbfb8aa3b, v170
	v_rcp_f32_e32 v2, v2
	s_mov_b64 vcc, s[8:9]
	v_exp_f32_e32 v170, v170
	v_rcp_f32_e32 v3, v3
	s_mov_b64 vcc, s[10:11]
	v_div_scale_f32 v180, s[12:13], 1.0, v169, 1.0
	v_cvt_pk_bf16_f32 v2, 0, v2
	v_rcp_f32_e32 v167, v167
	ds_write_b16_d16_hi v234, v2 offset:32768
	v_cvt_pk_bf16_f32 v2, 0, v3
	v_rcp_f32_e32 v168, v168
	ds_write_b16_d16_hi v234, v2 offset:33280
	v_cvt_pk_bf16_f32 v2, 0, v167
	ds_write_b16_d16_hi v234, v2 offset:33792
	v_cvt_pk_bf16_f32 v2, 0, v168
	v_add_f32_e32 v3, 1.0, v170
	s_mov_b64 vcc, s[12:13]
	ds_write_b16_d16_hi v234, v2 offset:34304
	v_rcp_f32_e32 v2, v169
	s_nop 0
	v_cvt_pk_bf16_f32 v2, 0, v2
	ds_write_b16_d16_hi v234, v2 offset:40960
	v_add_f32_e32 v167, v146, v164
	v_mul_f32_e32 v167, 0xbfb8aa3b, v167
	v_exp_f32_e32 v167, v167
	v_rcp_f32_e32 v2, v3
	v_add_f32_e32 v3, 1.0, v167
	v_cvt_pk_bf16_f32 v2, 0, v2
	ds_write_b16_d16_hi v234, v2 offset:41472
	v_add_f32_e32 v167, v147, v164
	v_mul_f32_e32 v167, 0xbfb8aa3b, v167
	v_exp_f32_e32 v167, v167
	v_rcp_f32_e32 v2, v3
	v_add_f32_e32 v3, 1.0, v167
	v_cvt_pk_bf16_f32 v2, 0, v2
	ds_write_b16_d16_hi v234, v2 offset:41984
	v_add_f32_e32 v167, v128, v164
	v_mul_f32_e32 v167, 0xbfb8aa3b, v167
	v_exp_f32_e32 v167, v167
	v_rcp_f32_e32 v2, v3
	v_add_f32_e32 v3, 1.0, v167
	v_cvt_pk_bf16_f32 v2, 0, v2
	ds_write_b16_d16_hi v234, v2 offset:42496
	v_add_f32_e32 v167, v129, v164
	v_mul_f32_e32 v167, 0xbfb8aa3b, v167
	v_exp_f32_e32 v167, v167
	v_rcp_f32_e32 v2, v3
	v_add_f32_e32 v3, 1.0, v167
	v_cvt_pk_bf16_f32 v2, 0, v2
	ds_write_b16_d16_hi v234, v2 offset:49152
	v_add_f32_e32 v167, v130, v164
	v_mul_f32_e32 v167, 0xbfb8aa3b, v167
	v_exp_f32_e32 v167, v167
	v_rcp_f32_e32 v2, v3
	v_add_f32_e32 v3, 1.0, v167
	v_cvt_pk_bf16_f32 v2, 0, v2
	ds_write_b16_d16_hi v234, v2 offset:49664
	v_add_f32_e32 v167, v131, v164
	v_mul_f32_e32 v167, 0xbfb8aa3b, v167
	v_exp_f32_e32 v167, v167
	v_rcp_f32_e32 v2, v3
	v_add_f32_e32 v3, 1.0, v167
	v_cvt_pk_bf16_f32 v2, 0, v2
	ds_write_b16_d16_hi v234, v2 offset:50176
	v_add_f32_e32 v167, v112, v164
	v_mul_f32_e32 v167, 0xbfb8aa3b, v167
	v_exp_f32_e32 v167, v167
	v_rcp_f32_e32 v2, v3
	v_add_f32_e32 v3, 1.0, v167
	v_cvt_pk_bf16_f32 v2, 0, v2
	ds_write_b16_d16_hi v234, v2 offset:50688
	v_add_f32_e32 v167, v113, v164
	v_mul_f32_e32 v167, 0xbfb8aa3b, v167
	v_exp_f32_e32 v167, v167
	v_rcp_f32_e32 v2, v3
	v_add_f32_e32 v3, 1.0, v167
	v_cvt_pk_bf16_f32 v2, 0, v2
	ds_write_b16_d16_hi v234, v2 offset:57344
	v_add_f32_e32 v167, v114, v164
	v_mul_f32_e32 v167, 0xbfb8aa3b, v167
	v_exp_f32_e32 v167, v167
	v_rcp_f32_e32 v2, v3
	v_add_f32_e32 v3, 1.0, v167
	v_cvt_pk_bf16_f32 v2, 0, v2
	ds_write_b16_d16_hi v234, v2 offset:57856
	v_add_f32_e32 v164, v115, v164
	v_mul_f32_e32 v164, 0xbfb8aa3b, v164
	v_exp_f32_e32 v164, v164
	v_rcp_f32_e32 v2, v3
	v_add_f32_e32 v3, 1.0, v164
	v_cvt_pk_bf16_f32 v2, 0, v2
	ds_write_b16_d16_hi v234, v2 offset:58368
	s_waitcnt vmcnt(2)
	v_add_f32_e32 v164, v156, v165
	v_mul_f32_e32 v164, 0xbfb8aa3b, v164
	v_exp_f32_e32 v164, v164
	v_rcp_f32_e32 v2, v3
	v_add_f32_e32 v3, 1.0, v164
	v_cvt_pk_bf16_f32 v2, 0, v2
	ds_write_b16_d16_hi v234, v2 offset:58880
	v_add_f32_e32 v164, v157, v165
	v_mul_f32_e32 v164, 0xbfb8aa3b, v164
	v_exp_f32_e32 v164, v164
	v_rcp_f32_e32 v2, v3
	v_add_f32_e32 v3, 1.0, v164
	v_cvt_pk_bf16_f32 v2, 0, v2
	ds_write_b16_d16_hi v234, v2 offset:34816
	v_add_f32_e32 v164, v158, v165
	v_mul_f32_e32 v164, 0xbfb8aa3b, v164
	v_exp_f32_e32 v164, v164
	v_rcp_f32_e32 v2, v3
	v_add_f32_e32 v3, 1.0, v164
	v_cvt_pk_bf16_f32 v2, 0, v2
	ds_write_b16_d16_hi v234, v2 offset:35328
	v_add_f32_e32 v164, v159, v165
	v_mul_f32_e32 v164, 0xbfb8aa3b, v164
	v_exp_f32_e32 v164, v164
	v_rcp_f32_e32 v2, v3
	v_add_f32_e32 v3, 1.0, v164
	v_cvt_pk_bf16_f32 v2, 0, v2
	ds_write_b16_d16_hi v234, v2 offset:35840
	v_add_f32_e32 v164, v140, v165
	v_mul_f32_e32 v164, 0xbfb8aa3b, v164
	v_exp_f32_e32 v164, v164
	v_rcp_f32_e32 v2, v3
	v_add_f32_e32 v3, 1.0, v164
	v_cvt_pk_bf16_f32 v2, 0, v2
	ds_write_b16_d16_hi v234, v2 offset:36352
	v_add_f32_e32 v164, v141, v165
	v_mul_f32_e32 v164, 0xbfb8aa3b, v164
	v_exp_f32_e32 v164, v164
	v_rcp_f32_e32 v2, v3
	v_add_f32_e32 v3, 1.0, v164
	v_cvt_pk_bf16_f32 v2, 0, v2
	ds_write_b16_d16_hi v234, v2 offset:43008
	v_add_f32_e32 v164, v142, v165
	v_mul_f32_e32 v164, 0xbfb8aa3b, v164
	v_exp_f32_e32 v164, v164
	v_rcp_f32_e32 v2, v3
	v_add_f32_e32 v3, 1.0, v164
	v_cvt_pk_bf16_f32 v2, 0, v2
	ds_write_b16_d16_hi v234, v2 offset:43520
; __device__ void phase_merge(const Params& p, int layer, char* smem) {
;     ...
; #pragma unroll
;             for (int n = 0; n < 4; ++n) {
;               float bm = bmp[seg * 1024 + n * 16];
; #pragma unroll
;               for (int m = 0; m < 4; ++m)
; #pragma unroll
;                 for (int j = 0; j < 4; ++j) {
;                   GL[((m * 4 + n) * 4 + j) * 256] = f2bf(1.f / (1.f + __expf(-(acc[m][n][j] + bm))));
;                   acc[m][n][j] = 0.f;
;                 }
;             }
	v_add_f32_e32 v164, v143, v165
	v_mul_f32_e32 v164, 0xbfb8aa3b, v164
	v_exp_f32_e32 v164, v164
	v_rcp_f32_e32 v2, v3
	v_add_f32_e32 v3, 1.0, v164
	v_cvt_pk_bf16_f32 v2, 0, v2
	ds_write_b16_d16_hi v234, v2 offset:44032
	v_add_f32_e32 v164, v124, v165
	v_mul_f32_e32 v164, 0xbfb8aa3b, v164
	v_exp_f32_e32 v164, v164
	v_rcp_f32_e32 v2, v3
	v_add_f32_e32 v3, 1.0, v164
	v_cvt_pk_bf16_f32 v2, 0, v2
	ds_write_b16_d16_hi v234, v2 offset:44544
	v_add_f32_e32 v164, v125, v165
	v_mul_f32_e32 v164, 0xbfb8aa3b, v164
	v_exp_f32_e32 v164, v164
	v_rcp_f32_e32 v2, v3
	v_add_f32_e32 v3, 1.0, v164
	v_cvt_pk_bf16_f32 v2, 0, v2
	ds_write_b16_d16_hi v234, v2 offset:51200
	v_add_f32_e32 v164, v126, v165
	v_mul_f32_e32 v164, 0xbfb8aa3b, v164
	v_exp_f32_e32 v164, v164
	v_rcp_f32_e32 v2, v3
	v_add_f32_e32 v3, 1.0, v164
	v_cvt_pk_bf16_f32 v2, 0, v2
	ds_write_b16_d16_hi v234, v2 offset:51712
	v_add_f32_e32 v164, v127, v165
	v_mul_f32_e32 v164, 0xbfb8aa3b, v164
	v_exp_f32_e32 v164, v164
	v_rcp_f32_e32 v2, v3
	v_add_f32_e32 v3, 1.0, v164
	v_cvt_pk_bf16_f32 v2, 0, v2
	ds_write_b16_d16_hi v234, v2 offset:52224
	v_add_f32_e32 v164, v108, v165
	v_mul_f32_e32 v164, 0xbfb8aa3b, v164
	v_exp_f32_e32 v164, v164
	v_rcp_f32_e32 v2, v3
	v_add_f32_e32 v3, 1.0, v164
	v_cvt_pk_bf16_f32 v2, 0, v2
	ds_write_b16_d16_hi v234, v2 offset:52736
	v_add_f32_e32 v164, v109, v165
	v_mul_f32_e32 v164, 0xbfb8aa3b, v164
	v_exp_f32_e32 v164, v164
	v_rcp_f32_e32 v2, v3
	v_add_f32_e32 v3, 1.0, v164
	v_cvt_pk_bf16_f32 v2, 0, v2
	ds_write_b16_d16_hi v234, v2 offset:59392
	v_add_f32_e32 v164, v110, v165
	v_mul_f32_e32 v164, 0xbfb8aa3b, v164
	v_exp_f32_e32 v164, v164
	v_rcp_f32_e32 v2, v3
	v_add_f32_e32 v3, 1.0, v164
	v_cvt_pk_bf16_f32 v2, 0, v2
	ds_write_b16_d16_hi v234, v2 offset:59904
	v_add_f32_e32 v164, v111, v165
	v_mul_f32_e32 v164, 0xbfb8aa3b, v164
	v_exp_f32_e32 v164, v164
	v_rcp_f32_e32 v2, v3
	v_add_f32_e32 v3, 1.0, v164
	v_cvt_pk_bf16_f32 v2, 0, v2
	ds_write_b16_d16_hi v234, v2 offset:60416
	s_waitcnt vmcnt(1)
	v_add_f32_e32 v164, v152, v166
	v_mul_f32_e32 v164, 0xbfb8aa3b, v164
	v_exp_f32_e32 v164, v164
	v_rcp_f32_e32 v2, v3
	v_add_f32_e32 v3, 1.0, v164
	v_cvt_pk_bf16_f32 v2, 0, v2
	ds_write_b16_d16_hi v234, v2 offset:60928
	v_add_f32_e32 v164, v153, v166
	v_mul_f32_e32 v164, 0xbfb8aa3b, v164
	v_exp_f32_e32 v164, v164
	v_rcp_f32_e32 v2, v3
	v_add_f32_e32 v3, 1.0, v164
	v_cvt_pk_bf16_f32 v2, 0, v2
	ds_write_b16_d16_hi v234, v2 offset:36864
	v_add_f32_e32 v164, v154, v166
	v_mul_f32_e32 v164, 0xbfb8aa3b, v164
	v_exp_f32_e32 v164, v164
	v_rcp_f32_e32 v2, v3
	v_add_f32_e32 v3, 1.0, v164
	v_cvt_pk_bf16_f32 v2, 0, v2
	ds_write_b16_d16_hi v234, v2 offset:37376
	v_add_f32_e32 v164, v155, v166
	v_mul_f32_e32 v164, 0xbfb8aa3b, v164
	v_exp_f32_e32 v164, v164
	v_rcp_f32_e32 v2, v3
	v_add_f32_e32 v3, 1.0, v164
	v_cvt_pk_bf16_f32 v2, 0, v2
	ds_write_b16_d16_hi v234, v2 offset:37888
	v_add_f32_e32 v164, v136, v166
	v_mul_f32_e32 v164, 0xbfb8aa3b, v164
	v_exp_f32_e32 v164, v164
	v_rcp_f32_e32 v2, v3
	v_add_f32_e32 v3, 1.0, v164
	v_cvt_pk_bf16_f32 v2, 0, v2
	ds_write_b16_d16_hi v234, v2 offset:38400
	v_add_f32_e32 v164, v137, v166
	v_mul_f32_e32 v164, 0xbfb8aa3b, v164
	v_exp_f32_e32 v164, v164
	v_rcp_f32_e32 v2, v3
	v_add_f32_e32 v3, 1.0, v164
	v_cvt_pk_bf16_f32 v2, 0, v2
	ds_write_b16_d16_hi v234, v2 offset:45056
	v_add_f32_e32 v164, v138, v166
	v_mul_f32_e32 v164, 0xbfb8aa3b, v164
	v_exp_f32_e32 v164, v164
	v_rcp_f32_e32 v2, v3
	v_add_f32_e32 v3, 1.0, v164
	v_cvt_pk_bf16_f32 v2, 0, v2
	ds_write_b16_d16_hi v234, v2 offset:45568
	v_add_f32_e32 v164, v139, v166
	v_mul_f32_e32 v164, 0xbfb8aa3b, v164
	v_exp_f32_e32 v164, v164
	v_rcp_f32_e32 v2, v3
	v_add_f32_e32 v3, 1.0, v164
	v_cvt_pk_bf16_f32 v2, 0, v2
	ds_write_b16_d16_hi v234, v2 offset:46080
	v_add_f32_e32 v164, v120, v166
	v_mul_f32_e32 v164, 0xbfb8aa3b, v164
	v_exp_f32_e32 v164, v164
	v_rcp_f32_e32 v2, v3
	v_add_f32_e32 v3, 1.0, v164
	v_cvt_pk_bf16_f32 v2, 0, v2
	ds_write_b16_d16_hi v234, v2 offset:46592
	v_add_f32_e32 v164, v121, v166
	v_mul_f32_e32 v164, 0xbfb8aa3b, v164
	v_exp_f32_e32 v164, v164
	v_rcp_f32_e32 v2, v3
	v_add_f32_e32 v3, 1.0, v164
	v_cvt_pk_bf16_f32 v2, 0, v2
	ds_write_b16_d16_hi v234, v2 offset:53248
	v_add_f32_e32 v164, v122, v166
	v_mul_f32_e32 v164, 0xbfb8aa3b, v164
	v_exp_f32_e32 v164, v164
	v_rcp_f32_e32 v2, v3
	v_add_f32_e32 v3, 1.0, v164
	v_cvt_pk_bf16_f32 v2, 0, v2
	ds_write_b16_d16_hi v234, v2 offset:53760
	v_add_f32_e32 v164, v123, v166
	v_mul_f32_e32 v164, 0xbfb8aa3b, v164
	v_exp_f32_e32 v164, v164
	v_rcp_f32_e32 v2, v3
	v_add_f32_e32 v3, 1.0, v164
	v_cvt_pk_bf16_f32 v2, 0, v2
	ds_write_b16_d16_hi v234, v2 offset:54272
	v_add_f32_e32 v164, v100, v166
	v_mul_f32_e32 v164, 0xbfb8aa3b, v164
	v_exp_f32_e32 v164, v164
	v_rcp_f32_e32 v2, v3
	v_add_f32_e32 v3, 1.0, v164
	v_cvt_pk_bf16_f32 v2, 0, v2
	ds_write_b16_d16_hi v234, v2 offset:54784
	v_add_f32_e32 v164, v101, v166
	v_mul_f32_e32 v164, 0xbfb8aa3b, v164
	v_exp_f32_e32 v164, v164
	v_rcp_f32_e32 v2, v3
	v_add_f32_e32 v3, 1.0, v164
	v_cvt_pk_bf16_f32 v2, 0, v2
	ds_write_b16_d16_hi v234, v2 offset:61440
	v_add_f32_e32 v164, v102, v166
	v_mul_f32_e32 v164, 0xbfb8aa3b, v164
	v_exp_f32_e32 v164, v164
	v_rcp_f32_e32 v2, v3
	v_add_f32_e32 v3, 1.0, v164
	v_cvt_pk_bf16_f32 v2, 0, v2
	ds_write_b16_d16_hi v234, v2 offset:61952
	v_add_f32_e32 v164, v103, v166
	v_mul_f32_e32 v164, 0xbfb8aa3b, v164
	v_exp_f32_e32 v164, v164
	v_rcp_f32_e32 v2, v3
	v_add_f32_e32 v3, 1.0, v164
	v_cvt_pk_bf16_f32 v2, 0, v2
	ds_write_b16_d16_hi v234, v2 offset:62464
	s_waitcnt vmcnt(0)
; __device__ void phase_merge(const Params& p, int layer, char* smem) {
;     ...
; #pragma unroll
;             for (int n = 0; n < 4; ++n) {
;               float bm = bmp[seg * 1024 + n * 16];
; #pragma unroll
;               for (int m = 0; m < 4; ++m)
; #pragma unroll
;                 for (int j = 0; j < 4; ++j) {
;                   GL[((m * 4 + n) * 4 + j) * 256] = f2bf(1.f / (1.f + __expf(-(acc[m][n][j] + bm))));
;                   acc[m][n][j] = 0.f;
;                 }
;             }
	v_add_f32_e32 v164, v148, v1
	v_mul_f32_e32 v164, 0xbfb8aa3b, v164
	v_exp_f32_e32 v164, v164
	v_rcp_f32_e32 v2, v3
	v_add_f32_e32 v3, 1.0, v164
	v_cvt_pk_bf16_f32 v2, 0, v2
	ds_write_b16_d16_hi v234, v2 offset:62976
	v_add_f32_e32 v164, v149, v1
	v_mul_f32_e32 v164, 0xbfb8aa3b, v164
	v_exp_f32_e32 v164, v164
	v_rcp_f32_e32 v2, v3
	v_add_f32_e32 v3, 1.0, v164
	v_cvt_pk_bf16_f32 v2, 0, v2
	ds_write_b16_d16_hi v234, v2 offset:38912
	v_add_f32_e32 v164, v150, v1
	v_mul_f32_e32 v164, 0xbfb8aa3b, v164
	v_exp_f32_e32 v164, v164
	v_rcp_f32_e32 v2, v3
	v_add_f32_e32 v3, 1.0, v164
	v_cvt_pk_bf16_f32 v2, 0, v2
	ds_write_b16_d16_hi v234, v2 offset:39424
	v_add_f32_e32 v164, v151, v1
	v_mul_f32_e32 v164, 0xbfb8aa3b, v164
	v_exp_f32_e32 v164, v164
	v_rcp_f32_e32 v2, v3
	v_add_f32_e32 v3, 1.0, v164
	v_cvt_pk_bf16_f32 v2, 0, v2
	ds_write_b16_d16_hi v234, v2 offset:39936
	v_add_f32_e32 v164, v132, v1
	v_mul_f32_e32 v164, 0xbfb8aa3b, v164
	v_exp_f32_e32 v164, v164
	v_rcp_f32_e32 v2, v3
	v_add_f32_e32 v3, 1.0, v164
	v_cvt_pk_bf16_f32 v2, 0, v2
	ds_write_b16_d16_hi v234, v2 offset:40448
	v_add_f32_e32 v164, v133, v1
	v_mul_f32_e32 v164, 0xbfb8aa3b, v164
	v_exp_f32_e32 v164, v164
	v_rcp_f32_e32 v2, v3
	v_add_f32_e32 v3, 1.0, v164
	v_cvt_pk_bf16_f32 v2, 0, v2
	ds_write_b16_d16_hi v234, v2 offset:47104
	v_add_f32_e32 v164, v134, v1
	v_mul_f32_e32 v164, 0xbfb8aa3b, v164
	v_exp_f32_e32 v164, v164
	v_rcp_f32_e32 v2, v3
	v_add_f32_e32 v3, 1.0, v164
	v_cvt_pk_bf16_f32 v2, 0, v2
	ds_write_b16_d16_hi v234, v2 offset:47616
	v_add_f32_e32 v164, v135, v1
	v_mul_f32_e32 v164, 0xbfb8aa3b, v164
	v_exp_f32_e32 v164, v164
	v_rcp_f32_e32 v2, v3
	v_add_f32_e32 v3, 1.0, v164
	v_cvt_pk_bf16_f32 v2, 0, v2
	ds_write_b16_d16_hi v234, v2 offset:48128
	v_add_f32_e32 v164, v116, v1
	v_mul_f32_e32 v164, 0xbfb8aa3b, v164
	v_exp_f32_e32 v164, v164
	v_rcp_f32_e32 v2, v3
	v_add_f32_e32 v3, 1.0, v164
	v_cvt_pk_bf16_f32 v2, 0, v2
	ds_write_b16_d16_hi v234, v2 offset:48640
	v_add_f32_e32 v164, v117, v1
	v_mul_f32_e32 v164, 0xbfb8aa3b, v164
	v_exp_f32_e32 v164, v164
	v_rcp_f32_e32 v2, v3
	v_add_f32_e32 v3, 1.0, v164
	v_cvt_pk_bf16_f32 v2, 0, v2
	ds_write_b16_d16_hi v234, v2 offset:55296
	v_add_f32_e32 v164, v118, v1
	v_mul_f32_e32 v164, 0xbfb8aa3b, v164
	v_exp_f32_e32 v164, v164
	v_rcp_f32_e32 v2, v3
	v_add_f32_e32 v3, 1.0, v164
	v_cvt_pk_bf16_f32 v2, 0, v2
	ds_write_b16_d16_hi v234, v2 offset:55808
	v_add_f32_e32 v164, v119, v1
	v_mul_f32_e32 v164, 0xbfb8aa3b, v164
	v_exp_f32_e32 v164, v164
	v_rcp_f32_e32 v2, v3
	v_add_f32_e32 v3, 1.0, v164
	v_cvt_pk_bf16_f32 v2, 0, v2
	ds_write_b16_d16_hi v234, v2 offset:56320
	v_add_f32_e32 v164, v104, v1
	v_mul_f32_e32 v164, 0xbfb8aa3b, v164
	v_exp_f32_e32 v164, v164
	v_rcp_f32_e32 v2, v3
	v_add_f32_e32 v3, 1.0, v164
	v_cvt_pk_bf16_f32 v2, 0, v2
	ds_write_b16_d16_hi v234, v2 offset:56832
	v_add_f32_e32 v164, v105, v1
	v_mul_f32_e32 v164, 0xbfb8aa3b, v164
	v_exp_f32_e32 v164, v164
	v_rcp_f32_e32 v2, v3
	v_add_f32_e32 v3, 1.0, v164
	v_cvt_pk_bf16_f32 v2, 0, v2
	ds_write_b16_d16_hi v234, v2 offset:63488
	v_add_f32_e32 v164, v106, v1
	v_mul_f32_e32 v164, 0xbfb8aa3b, v164
	v_exp_f32_e32 v164, v164
	v_rcp_f32_e32 v2, v3
	v_add_f32_e32 v3, 1.0, v164
	v_cvt_pk_bf16_f32 v2, 0, v2
	ds_write_b16_d16_hi v234, v2 offset:64000
	v_add_f32_e32 v1, v107, v1
	v_mul_f32_e32 v1, 0xbfb8aa3b, v1
	v_exp_f32_e32 v1, v1
	v_rcp_f32_e32 v2, v3
	s_nop 0
	v_cvt_pk_bf16_f32 v2, 0, v2
	v_add_f32_e32 v3, 1.0, v1
	ds_write_b16_d16_hi v234, v2 offset:64512
	v_mov_b32_e32 v1, v0
	v_mov_b32_e32 v2, v0
	v_rcp_f32_e32 v3, v3
	s_nop 0
	v_cvt_pk_bf16_f32 v3, 0, v3
	ds_write_b16_d16_hi v234, v3 offset:65024
	s_mov_b64 s[6:7], -1

; template <int WM, int WN> ...
;     ...
; #pragma unroll
;   for (int n = 0; n < 4; ++n) fb0[n] = LDSF(cur + boff + n * 1024);
; #pragma unroll
;   for (int m = 0; m < 4; ++m) fa0[m] = LDSF(cur + aoff + m * 1024);
;   acc[3][0] = MFMA16(pa, pb0, acc[3][0]);
;   acc[3][1] = MFMA16(pa, pb1, acc[3][1]);
;   acc[3][2] = MFMA16(pa, pb2, acc[3][2]);
;   acc[3][3] = MFMA16(pa, pb3, acc[3][3]);
; #pragma unroll
;   for (int n = 0; n < 4; ++n) acc[0][n] = MFMA16(fa0[0], fb0[n], acc[0][n]);
; #pragma unroll
;   for (int m = 0; m < 4; ++m) fa1[m] = LDSF(cur + aoff + APAN + m * 1024);
; #pragma unroll
;   for (int n = 0; n < 4; ++n) acc[1][n] = MFMA16(fa0[1], fb0[n], acc[1][n]);
; #pragma unroll
;   for (int n = 0; n < 4; ++n) fb1[n] = LDSF(cur + boff + BPAN + n * 1024);
; #pragma unroll
;   for (int n = 0; n < 4; ++n) acc[2][n] = MFMA16(fa0[2], fb0[n], acc[2][n]);
;   *reinterpret_cast<uint4*>(nxt + wao) = a0;
;   *reinterpret_cast<uint4*>(nxt + wao + 32 * 64) = a1;
; #pragma unroll
;   for (int n = 0; n < 4; ++n) acc[3][n] = MFMA16(fa0[3], fb0[n], acc[3][n]);
;   *reinterpret_cast<uint4*>(nxt + wao + 64 * 64) = a2;
;   *reinterpret_cast<uint4*>(nxt + wao + 96 * 64) = a3;
; #pragma unroll
;   for (int n = 0; n < 4; ++n) acc[0][n] = MFMA16(fa1[0], fb1[n], acc[0][n]);
;   *reinterpret_cast<uint4*>(nxt + wbo) = b0;
;   *reinterpret_cast<uint4*>(nxt + wbo + 32 * 64) = b1;
; #pragma unroll
;   for (int n = 0; n < 4; ++n) acc[1][n] = MFMA16(fa1[1], fb1[n], acc[1][n]);
;   *reinterpret_cast<uint4*>(nxt + wbo + 64 * 64) = b2;
;   *reinterpret_cast<uint4*>(nxt + wbo + 96 * 64) = b3;
; #pragma unroll
;   for (int n = 0; n < 4; ++n) acc[2][n] = MFMA16(fa1[2], fb1[n], acc[2][n]);
;   pa = fa1[3];
;   pb0 = fb1[0]; pb1 = fb1[1]; pb2 = fb1[2]; pb3 = fb1[3];
;   SGB_(0x100, 5);
;   SGB_(0x008, 4);
; #pragma unroll
;   for (int i_ = 0; i_ < 11; ++i_) { SGB_(0x008, 1); SGB_(0x100, 1); }
; #pragma unroll
;   for (int i_ = 0; i_ < 8; ++i_) { SGB_(0x008, 2); SGB_(0x200, 1); SGB_(0x020, 1); }
;   SGB_(0x008, 1);
; template <int WM, int WN, typename SrcF, typename PostF>
; __device__ __forceinline__ void gemm_stream(const int nsteps, SrcF src, PostF post, f32x4 (&acc)[WM][WN], char* smem) {
;     ...
;   for (int kt = 0; kt < nsteps; kt += 2) {
;     {
;       TileSrc s = src(min(kt + 2, nsteps - 1));
;       GLOAD_TILE(xa, s.a, s.lda, ACH);
;       GLOAD_TILE(xb, s.b, s.ldb, BCH);
;     }
.LBB0_1281:
	s_add_i32 s27, s5, 2
	s_add_i32 s5, s5, 4
	s_min_u32 s5, s5, 15
	s_lshl_b32 s5, s5, 7
	s_add_u32 s92, s8, s5
	s_addc_u32 s93, s9, 0
	s_add_u32 s94, s10, s5
	s_addc_u32 s95, s11, 0
	ds_read_b128 v[144:147], v124
	ds_read_b128 v[128:131], v125 offset:16512
	ds_read_b128 v[132:135], v125 offset:17536
	ds_read_b128 v[136:139], v125 offset:18560
	ds_read_b128 v[140:143], v125 offset:19584
	v_mfma_f32_16x16x32_bf16 v[64:67], v[48:51], v[64:67], v[92:95]
	v_mfma_f32_16x16x32_bf16 v[88:91], v[48:51], v[104:107], v[88:91]
	s_waitcnt vmcnt(7)
	ds_write_b128 v126, v[32:35] offset:33024
	global_load_dwordx4 v[32:35], v116, s[92:93]
	s_add_u32 s34, s8, s5
	s_addc_u32 s35, s9, 0
	v_mfma_f32_16x16x32_bf16 v[80:83], v[48:51], v[112:115], v[80:83]
	v_mfma_f32_16x16x32_bf16 v[48:51], v[48:51], v[108:111], v[56:59]
	s_waitcnt lgkmcnt(4)
	v_mfma_f32_16x16x32_bf16 v[56:59], v[144:147], v[128:131], v[100:103]
	ds_read_b128 v[92:95], v124 offset:1024
	s_waitcnt lgkmcnt(4)
	v_mfma_f32_16x16x32_bf16 v[96:99], v[144:147], v[132:135], v[96:99]
	s_waitcnt vmcnt(7)
	ds_write_b128 v126, v[20:23] offset:35072
	global_load_dwordx4 v[20:23], v118, s[92:93]
	ds_read_b128 v[100:103], v124 offset:2048
	s_waitcnt lgkmcnt(5)
	v_mfma_f32_16x16x32_bf16 v[84:87], v[144:147], v[136:139], v[84:87]
	ds_read_b128 v[104:107], v124 offset:3072
	s_waitcnt lgkmcnt(5)
	v_mfma_f32_16x16x32_bf16 v[76:79], v[144:147], v[140:143], v[76:79]
	ds_read_b128 v[108:111], v124 offset:8256
	s_waitcnt lgkmcnt(4)
	v_mfma_f32_16x16x32_bf16 v[72:75], v[92:95], v[128:131], v[72:75]
	ds_read_b128 v[112:115], v124 offset:9280
	v_mfma_f32_16x16x32_bf16 v[68:71], v[92:95], v[132:135], v[68:71]
	ds_read_b128 v[144:147], v124 offset:10304
	v_mfma_f32_16x16x32_bf16 v[60:63], v[92:95], v[136:139], v[60:63]
	s_waitcnt vmcnt(7)
	ds_write_b128 v126, v[16:19] offset:37120
	global_load_dwordx4 v[16:19], v120, s[92:93]
	ds_read_b128 v[148:151], v124 offset:11328
	v_mfma_f32_16x16x32_bf16 v[52:55], v[92:95], v[140:143], v[52:55]
	ds_read_b128 v[92:95], v125 offset:24768
	s_waitcnt lgkmcnt(7)
	v_mfma_f32_16x16x32_bf16 v[44:47], v[100:103], v[128:131], v[44:47]
	ds_read_b128 v[152:155], v125 offset:25792
	v_mfma_f32_16x16x32_bf16 v[40:43], v[100:103], v[132:135], v[40:43]
	ds_read_b128 v[156:159], v125 offset:26816
	v_mfma_f32_16x16x32_bf16 v[36:39], v[100:103], v[136:139], v[36:39]
	s_waitcnt vmcnt(7)
	ds_write_b128 v126, v[24:27] offset:39168
	global_load_dwordx4 v[24:27], v122, s[92:93]
	ds_read_b128 v[160:163], v125 offset:27840
	v_mfma_f32_16x16x32_bf16 v[28:31], v[100:103], v[140:143], v[28:31]
	s_waitcnt lgkmcnt(10)
	v_mfma_f32_16x16x32_bf16 v[64:67], v[104:107], v[128:131], v[64:67]
	v_mfma_f32_16x16x32_bf16 v[88:91], v[104:107], v[132:135], v[88:91]
	v_mfma_f32_16x16x32_bf16 v[80:83], v[104:107], v[136:139], v[80:83]
	v_mfma_f32_16x16x32_bf16 v[48:51], v[104:107], v[140:143], v[48:51]
	s_waitcnt vmcnt(7)
	ds_write_b128 v126, v[12:15] offset:49536
	global_load_dwordx4 v[12:15], v116, s[94:95]
	s_waitcnt lgkmcnt(5)
	v_mfma_f32_16x16x32_bf16 v[56:59], v[108:111], v[92:95], v[56:59]
	s_add_u32 s34, s10, s5
	s_addc_u32 s35, s11, 0
	s_waitcnt lgkmcnt(4)
	v_mfma_f32_16x16x32_bf16 v[96:99], v[108:111], v[152:155], v[96:99]
	s_min_u32 s5, s27, 12
	s_lshl_b32 s5, s5, 7
	s_waitcnt lgkmcnt(3)
	v_mfma_f32_16x16x32_bf16 v[84:87], v[108:111], v[156:159], v[84:87]
	s_waitcnt lgkmcnt(1)
	v_mfma_f32_16x16x32_bf16 v[76:79], v[108:111], v[160:163], v[76:79]
	s_waitcnt vmcnt(7)
	ds_write_b128 v126, v[8:11] offset:51584
	global_load_dwordx4 v[8:11], v118, s[94:95]
	v_mfma_f32_16x16x32_bf16 v[72:75], v[112:115], v[92:95], v[72:75]
	v_mfma_f32_16x16x32_bf16 v[68:71], v[112:115], v[152:155], v[68:71]
	v_mfma_f32_16x16x32_bf16 v[60:63], v[112:115], v[156:159], v[60:63]
	v_mfma_f32_16x16x32_bf16 v[52:55], v[112:115], v[160:163], v[52:55]
	v_mfma_f32_16x16x32_bf16 v[44:47], v[144:147], v[92:95], v[44:47]
	s_waitcnt vmcnt(7)
	ds_write_b128 v126, v[4:7] offset:53632
	global_load_dwordx4 v[4:7], v120, s[94:95]
	v_mfma_f32_16x16x32_bf16 v[40:43], v[144:147], v[152:155], v[40:43]
	s_add_u32 s34, s8, s5
	s_addc_u32 s35, s9, 0
	s_add_u32 s36, s10, s5
	v_mfma_f32_16x16x32_bf16 v[36:39], v[144:147], v[156:159], v[36:39]
	s_addc_u32 s37, s11, 0
	v_mfma_f32_16x16x32_bf16 v[28:31], v[144:147], v[160:163], v[28:31]
	v_mfma_f32_16x16x32_bf16 v[92:95], v[148:151], v[92:95], v[64:67]
	s_waitcnt vmcnt(7)
	ds_write_b128 v126, v[0:3] offset:55680
	global_load_dwordx4 v[0:3], v122, s[94:95]
	v_mfma_f32_16x16x32_bf16 v[88:91], v[148:151], v[152:155], v[88:91]
	v_mfma_f32_16x16x32_bf16 v[80:83], v[148:151], v[156:159], v[80:83]
	v_mfma_f32_16x16x32_bf16 v[100:103], v[148:151], v[160:163], v[48:51]
	s_waitcnt lgkmcnt(0)
	s_barrier
; template <int WM, int WN> ...
;     ...
; #pragma unroll
;   for (int n = 0; n < 4; ++n) fb0[n] = LDSF(cur + boff + n * 1024);
; #pragma unroll
;   for (int m = 0; m < 4; ++m) fa0[m] = LDSF(cur + aoff + m * 1024);
;   acc[3][0] = MFMA16(pa, pb0, acc[3][0]);
;   acc[3][1] = MFMA16(pa, pb1, acc[3][1]);
;   acc[3][2] = MFMA16(pa, pb2, acc[3][2]);
;   acc[3][3] = MFMA16(pa, pb3, acc[3][3]);
; #pragma unroll
;   for (int n = 0; n < 4; ++n) acc[0][n] = MFMA16(fa0[0], fb0[n], acc[0][n]);
; #pragma unroll
;   for (int m = 0; m < 4; ++m) fa1[m] = LDSF(cur + aoff + APAN + m * 1024);
; #pragma unroll
;   for (int n = 0; n < 4; ++n) acc[1][n] = MFMA16(fa0[1], fb0[n], acc[1][n]);
; #pragma unroll
;   for (int n = 0; n < 4; ++n) fb1[n] = LDSF(cur + boff + BPAN + n * 1024);
; #pragma unroll
;   for (int n = 0; n < 4; ++n) acc[2][n] = MFMA16(fa0[2], fb0[n], acc[2][n]);
;   *reinterpret_cast<uint4*>(nxt + wao) = a0;
;   *reinterpret_cast<uint4*>(nxt + wao + 32 * 64) = a1;
; #pragma unroll
;   for (int n = 0; n < 4; ++n) acc[3][n] = MFMA16(fa0[3], fb0[n], acc[3][n]);
;   *reinterpret_cast<uint4*>(nxt + wao + 64 * 64) = a2;
;   *reinterpret_cast<uint4*>(nxt + wao + 96 * 64) = a3;
; #pragma unroll
;   for (int n = 0; n < 4; ++n) acc[0][n] = MFMA16(fa1[0], fb1[n], acc[0][n]);
;   *reinterpret_cast<uint4*>(nxt + wbo) = b0;
;   *reinterpret_cast<uint4*>(nxt + wbo + 32 * 64) = b1;
; #pragma unroll
;   for (int n = 0; n < 4; ++n) acc[1][n] = MFMA16(fa1[1], fb1[n], acc[1][n]);
;   *reinterpret_cast<uint4*>(nxt + wbo + 64 * 64) = b2;
;   *reinterpret_cast<uint4*>(nxt + wbo + 96 * 64) = b3;
; #pragma unroll
;   for (int n = 0; n < 4; ++n) acc[2][n] = MFMA16(fa1[2], fb1[n], acc[2][n]);
;   pa = fa1[3];
;   pb0 = fb1[0]; pb1 = fb1[1]; pb2 = fb1[2]; pb3 = fb1[3];
;   SGB_(0x100, 5);
;   SGB_(0x008, 4);
; #pragma unroll
;   for (int i_ = 0; i_ < 11; ++i_) { SGB_(0x008, 1); SGB_(0x100, 1); }
; #pragma unroll
;   for (int i_ = 0; i_ < 8; ++i_) { SGB_(0x008, 2); SGB_(0x200, 1); SGB_(0x020, 1); }
;   SGB_(0x008, 1);
; template <int WM, int WN, typename SrcF, typename PostF>
; __device__ __forceinline__ void gemm_stream(const int nsteps, SrcF src, PostF post, f32x4 (&acc)[WM][WN], char* smem) {
;     ...
;     __syncthreads();
;     {
;       TileSrc s = src(min(kt + 3, nsteps - 1));
;       GLOAD_TILE(ya, s.a, s.lda, ACH);
;       GLOAD_TILE(yb, s.b, s.ldb, BCH);
;     }
	s_nop 0
	ds_read_b128 v[48:51], v124 offset:33024
	ds_read_b128 v[108:111], v125 offset:49536
	ds_read_b128 v[128:131], v125 offset:50560
	ds_read_b128 v[132:135], v125 offset:51584
	ds_read_b128 v[136:139], v125 offset:52608
	s_waitcnt lgkmcnt(3)
	v_mfma_f32_16x16x32_bf16 v[140:143], v[48:51], v[108:111], v[56:59]
	s_waitcnt lgkmcnt(2)
	v_mfma_f32_16x16x32_bf16 v[96:99], v[48:51], v[128:131], v[96:99]
	s_waitcnt vmcnt(7)
	ds_write_b128 v126, v[32:35]
	global_load_dwordx4 v[32:35], v116, s[34:35] offset:384
	s_waitcnt lgkmcnt(2)
	v_mfma_f32_16x16x32_bf16 v[84:87], v[48:51], v[132:135], v[84:87]
	s_waitcnt lgkmcnt(0)
	v_mfma_f32_16x16x32_bf16 v[76:79], v[48:51], v[136:139], v[76:79]
	ds_read_b128 v[48:51], v124 offset:34048
	s_waitcnt lgkmcnt(0)
	v_mfma_f32_16x16x32_bf16 v[72:75], v[48:51], v[108:111], v[72:75]
	s_waitcnt vmcnt(7)
	ds_write_b128 v126, v[20:23] offset:2048
	global_load_dwordx4 v[20:23], v118, s[34:35] offset:384
	ds_read_b128 v[56:59], v124 offset:35072
	v_mfma_f32_16x16x32_bf16 v[68:71], v[48:51], v[128:131], v[68:71]
	ds_read_b128 v[144:147], v124 offset:36096
	v_mfma_f32_16x16x32_bf16 v[60:63], v[48:51], v[132:135], v[60:63]
	ds_read_b128 v[148:151], v124 offset:41280
	v_mfma_f32_16x16x32_bf16 v[52:55], v[48:51], v[136:139], v[52:55]
	ds_read_b128 v[152:155], v124 offset:42304
	s_waitcnt lgkmcnt(3)
	v_mfma_f32_16x16x32_bf16 v[44:47], v[56:59], v[108:111], v[44:47]
	s_waitcnt vmcnt(7)
	ds_write_b128 v126, v[16:19] offset:4096
	global_load_dwordx4 v[16:19], v120, s[34:35] offset:384
	ds_read_b128 v[156:159], v124 offset:43328
	v_mfma_f32_16x16x32_bf16 v[40:43], v[56:59], v[128:131], v[40:43]
	ds_read_b128 v[48:51], v124 offset:44352
	v_mfma_f32_16x16x32_bf16 v[36:39], v[56:59], v[132:135], v[36:39]
	ds_read_b128 v[64:67], v125 offset:57792
	v_mfma_f32_16x16x32_bf16 v[28:31], v[56:59], v[136:139], v[28:31]
	s_waitcnt vmcnt(7)
	ds_write_b128 v126, v[24:27] offset:6144
	global_load_dwordx4 v[24:27], v122, s[34:35] offset:384
	ds_read_b128 v[104:107], v125 offset:58816
	s_waitcnt lgkmcnt(8)
	v_mfma_f32_16x16x32_bf16 v[92:95], v[144:147], v[108:111], v[92:95]
	ds_read_b128 v[112:115], v125 offset:59840
	v_mfma_f32_16x16x32_bf16 v[88:91], v[144:147], v[128:131], v[88:91]
	ds_read_b128 v[108:111], v125 offset:60864
	v_mfma_f32_16x16x32_bf16 v[80:83], v[144:147], v[132:135], v[80:83]
	v_mfma_f32_16x16x32_bf16 v[56:59], v[144:147], v[136:139], v[100:103]
	s_waitcnt vmcnt(7)
	ds_write_b128 v126, v[12:15] offset:16512
	global_load_dwordx4 v[12:15], v116, s[36:37] offset:384
	s_waitcnt lgkmcnt(5)
	v_mfma_f32_16x16x32_bf16 v[100:103], v[148:151], v[64:67], v[140:143]
	s_waitcnt lgkmcnt(3)
	v_mfma_f32_16x16x32_bf16 v[96:99], v[148:151], v[104:107], v[96:99]
	s_waitcnt lgkmcnt(2)
	v_mfma_f32_16x16x32_bf16 v[84:87], v[148:151], v[112:115], v[84:87]
	s_waitcnt vmcnt(7)
	ds_write_b128 v126, v[8:11] offset:18560
	global_load_dwordx4 v[8:11], v118, s[36:37] offset:384
	s_waitcnt lgkmcnt(2)
	v_mfma_f32_16x16x32_bf16 v[76:79], v[148:151], v[108:111], v[76:79]
	v_mfma_f32_16x16x32_bf16 v[72:75], v[152:155], v[64:67], v[72:75]
	v_mfma_f32_16x16x32_bf16 v[68:71], v[152:155], v[104:107], v[68:71]
	v_mfma_f32_16x16x32_bf16 v[60:63], v[152:155], v[112:115], v[60:63]
	s_waitcnt vmcnt(7)
	ds_write_b128 v126, v[4:7] offset:20608
	global_load_dwordx4 v[4:7], v120, s[36:37] offset:384
	v_mfma_f32_16x16x32_bf16 v[52:55], v[152:155], v[108:111], v[52:55]
	v_mfma_f32_16x16x32_bf16 v[44:47], v[156:159], v[64:67], v[44:47]
	v_mfma_f32_16x16x32_bf16 v[40:43], v[156:159], v[104:107], v[40:43]
	s_waitcnt vmcnt(7)
	ds_write_b128 v126, v[0:3] offset:22656
	global_load_dwordx4 v[0:3], v122, s[36:37] offset:384
	v_mfma_f32_16x16x32_bf16 v[36:39], v[156:159], v[112:115], v[36:39]
	v_mfma_f32_16x16x32_bf16 v[28:31], v[156:159], v[108:111], v[28:31]
	s_cmp_lt_u32 s27, 12
	s_mov_b32 s5, s27
	s_waitcnt lgkmcnt(0)
	s_barrier
	s_cbranch_scc1 .LBB0_1281
	ds_read_b128 v[144:147], v124
	ds_read_b128 v[128:131], v125 offset:16512
	ds_read_b128 v[132:135], v125 offset:17536
	ds_read_b128 v[136:139], v125 offset:18560
	ds_read_b128 v[140:143], v125 offset:19584
	v_mfma_f32_16x16x32_bf16 v[64:67], v[48:51], v[64:67], v[92:95]
	s_add_i32 s27, s5, 2
	s_add_i32 s5, s5, 4
	s_min_u32 s5, s5, 15
	v_mfma_f32_16x16x32_bf16 v[88:91], v[48:51], v[104:107], v[88:91]
	s_lshl_b32 s5, s5, 7
	s_add_u32 s34, s8, s5
	s_addc_u32 s35, s9, 0
	v_mfma_f32_16x16x32_bf16 v[80:83], v[48:51], v[112:115], v[80:83]
	v_mfma_f32_16x16x32_bf16 v[48:51], v[48:51], v[108:111], v[56:59]
	s_waitcnt lgkmcnt(3)
	v_mfma_f32_16x16x32_bf16 v[56:59], v[144:147], v[128:131], v[100:103]
	ds_read_b128 v[92:95], v124 offset:1024
	s_waitcnt lgkmcnt(3)
	v_mfma_f32_16x16x32_bf16 v[96:99], v[144:147], v[132:135], v[96:99]
	ds_read_b128 v[100:103], v124 offset:2048
	s_waitcnt lgkmcnt(3)
	v_mfma_f32_16x16x32_bf16 v[84:87], v[144:147], v[136:139], v[84:87]
	ds_read_b128 v[104:107], v124 offset:3072
	s_waitcnt lgkmcnt(3)
	v_mfma_f32_16x16x32_bf16 v[76:79], v[144:147], v[140:143], v[76:79]
	ds_read_b128 v[108:111], v124 offset:8256
	s_waitcnt lgkmcnt(3)
	v_mfma_f32_16x16x32_bf16 v[72:75], v[92:95], v[128:131], v[72:75]
	ds_read_b128 v[112:115], v124 offset:9280
	v_mfma_f32_16x16x32_bf16 v[68:71], v[92:95], v[132:135], v[68:71]
	ds_read_b128 v[144:147], v124 offset:10304
	v_mfma_f32_16x16x32_bf16 v[60:63], v[92:95], v[136:139], v[60:63]
	ds_read_b128 v[148:151], v124 offset:11328
	v_mfma_f32_16x16x32_bf16 v[52:55], v[92:95], v[140:143], v[52:55]
	ds_read_b128 v[92:95], v125 offset:24768
	s_waitcnt lgkmcnt(6)
; template <int WM, int WN> ...
;     ...
; #pragma unroll
;   for (int n = 0; n < 4; ++n) fb0[n] = LDSF(cur + boff + n * 1024);
; #pragma unroll
;   for (int m = 0; m < 4; ++m) fa0[m] = LDSF(cur + aoff + m * 1024);
;   acc[3][0] = MFMA16(pa, pb0, acc[3][0]);
;   acc[3][1] = MFMA16(pa, pb1, acc[3][1]);
;   acc[3][2] = MFMA16(pa, pb2, acc[3][2]);
;   acc[3][3] = MFMA16(pa, pb3, acc[3][3]);
; #pragma unroll
;   for (int n = 0; n < 4; ++n) acc[0][n] = MFMA16(fa0[0], fb0[n], acc[0][n]);
; #pragma unroll
;   for (int m = 0; m < 4; ++m) fa1[m] = LDSF(cur + aoff + APAN + m * 1024);
; #pragma unroll
;   for (int n = 0; n < 4; ++n) acc[1][n] = MFMA16(fa0[1], fb0[n], acc[1][n]);
; #pragma unroll
;   for (int n = 0; n < 4; ++n) fb1[n] = LDSF(cur + boff + BPAN + n * 1024);
; #pragma unroll
;   for (int n = 0; n < 4; ++n) acc[2][n] = MFMA16(fa0[2], fb0[n], acc[2][n]);
;   *reinterpret_cast<uint4*>(nxt + wao) = a0;
;   *reinterpret_cast<uint4*>(nxt + wao + 32 * 64) = a1;
; #pragma unroll
;   for (int n = 0; n < 4; ++n) acc[3][n] = MFMA16(fa0[3], fb0[n], acc[3][n]);
;   *reinterpret_cast<uint4*>(nxt + wao + 64 * 64) = a2;
;   *reinterpret_cast<uint4*>(nxt + wao + 96 * 64) = a3;
; #pragma unroll
;   for (int n = 0; n < 4; ++n) acc[0][n] = MFMA16(fa1[0], fb1[n], acc[0][n]);
;   *reinterpret_cast<uint4*>(nxt + wbo) = b0;
;   *reinterpret_cast<uint4*>(nxt + wbo + 32 * 64) = b1;
; #pragma unroll
;   for (int n = 0; n < 4; ++n) acc[1][n] = MFMA16(fa1[1], fb1[n], acc[1][n]);
;   *reinterpret_cast<uint4*>(nxt + wbo + 64 * 64) = b2;
;   *reinterpret_cast<uint4*>(nxt + wbo + 96 * 64) = b3;
; #pragma unroll
;   for (int n = 0; n < 4; ++n) acc[2][n] = MFMA16(fa1[2], fb1[n], acc[2][n]);
;   pa = fa1[3];
;   pb0 = fb1[0]; pb1 = fb1[1]; pb2 = fb1[2]; pb3 = fb1[3];
;   SGB_(0x100, 5);
;   SGB_(0x008, 4);
; #pragma unroll
;   for (int i_ = 0; i_ < 11; ++i_) { SGB_(0x008, 1); SGB_(0x100, 1); }
; #pragma unroll
;   for (int i_ = 0; i_ < 8; ++i_) { SGB_(0x008, 2); SGB_(0x200, 1); SGB_(0x020, 1); }
;   SGB_(0x008, 1);
; template <int WM, int WN, typename SrcF, typename PostF>
; __device__ __forceinline__ void gemm_stream(const int nsteps, SrcF src, PostF post, f32x4 (&acc)[WM][WN], char* smem) {
;     ...
;   for (int kt = 0; kt < nsteps; kt += 2) {
;     {
;       TileSrc s = src(min(kt + 2, nsteps - 1));
;       GLOAD_TILE(xa, s.a, s.lda, ACH);
;       GLOAD_TILE(xb, s.b, s.ldb, BCH);
;     }
	v_mfma_f32_16x16x32_bf16 v[44:47], v[100:103], v[128:131], v[44:47]
	ds_read_b128 v[152:155], v125 offset:25792
	v_mfma_f32_16x16x32_bf16 v[40:43], v[100:103], v[132:135], v[40:43]
	ds_read_b128 v[156:159], v125 offset:26816
	v_mfma_f32_16x16x32_bf16 v[36:39], v[100:103], v[136:139], v[36:39]
	ds_read_b128 v[160:163], v125 offset:27840
	v_mfma_f32_16x16x32_bf16 v[28:31], v[100:103], v[140:143], v[28:31]
	s_waitcnt lgkmcnt(8)
	v_mfma_f32_16x16x32_bf16 v[64:67], v[104:107], v[128:131], v[64:67]
	s_waitcnt vmcnt(7)
	ds_write_b128 v126, v[32:35] offset:33024
	v_mfma_f32_16x16x32_bf16 v[88:91], v[104:107], v[132:135], v[88:91]
	v_mfma_f32_16x16x32_bf16 v[80:83], v[104:107], v[136:139], v[80:83]
	s_waitcnt vmcnt(6)
	ds_write_b128 v126, v[20:23] offset:35072
	v_mfma_f32_16x16x32_bf16 v[48:51], v[104:107], v[140:143], v[48:51]
	s_waitcnt lgkmcnt(5)
	v_mfma_f32_16x16x32_bf16 v[56:59], v[108:111], v[92:95], v[56:59]
	s_waitcnt vmcnt(5)
	ds_write_b128 v126, v[16:19] offset:37120
	s_add_u32 s34, s10, s5
	s_addc_u32 s35, s11, 0
	s_waitcnt lgkmcnt(5)
	v_mfma_f32_16x16x32_bf16 v[96:99], v[108:111], v[152:155], v[96:99]
	s_min_u32 s5, s27, 12
	s_lshl_b32 s5, s5, 7
	s_waitcnt lgkmcnt(4)
	v_mfma_f32_16x16x32_bf16 v[84:87], v[108:111], v[156:159], v[84:87]
	s_waitcnt vmcnt(4)
	ds_write_b128 v126, v[24:27] offset:39168
	s_waitcnt lgkmcnt(4)
	v_mfma_f32_16x16x32_bf16 v[76:79], v[108:111], v[160:163], v[76:79]
	v_mfma_f32_16x16x32_bf16 v[72:75], v[112:115], v[92:95], v[72:75]
	s_waitcnt vmcnt(3)
	ds_write_b128 v126, v[12:15] offset:49536
	v_mfma_f32_16x16x32_bf16 v[68:71], v[112:115], v[152:155], v[68:71]
	v_mfma_f32_16x16x32_bf16 v[60:63], v[112:115], v[156:159], v[60:63]
	s_waitcnt vmcnt(2)
	ds_write_b128 v126, v[8:11] offset:51584
	v_mfma_f32_16x16x32_bf16 v[52:55], v[112:115], v[160:163], v[52:55]
	v_mfma_f32_16x16x32_bf16 v[44:47], v[144:147], v[92:95], v[44:47]
	s_waitcnt vmcnt(1)
	ds_write_b128 v126, v[4:7] offset:53632
	v_mfma_f32_16x16x32_bf16 v[40:43], v[144:147], v[152:155], v[40:43]
	s_add_u32 s34, s8, s5
	s_addc_u32 s35, s9, 0
	s_add_u32 s36, s10, s5
	v_mfma_f32_16x16x32_bf16 v[36:39], v[144:147], v[156:159], v[36:39]
	s_waitcnt vmcnt(0)
	ds_write_b128 v126, v[0:3] offset:55680
	s_addc_u32 s37, s11, 0
	v_mfma_f32_16x16x32_bf16 v[28:31], v[144:147], v[160:163], v[28:31]
	v_mfma_f32_16x16x32_bf16 v[92:95], v[148:151], v[92:95], v[64:67]
	v_mfma_f32_16x16x32_bf16 v[88:91], v[148:151], v[152:155], v[88:91]
	v_mfma_f32_16x16x32_bf16 v[80:83], v[148:151], v[156:159], v[80:83]
	v_mfma_f32_16x16x32_bf16 v[100:103], v[148:151], v[160:163], v[48:51]
	s_waitcnt lgkmcnt(0)
	s_barrier
	s_nop 0
	ds_read_b128 v[48:51], v124 offset:33024
	ds_read_b128 v[108:111], v125 offset:49536
	ds_read_b128 v[128:131], v125 offset:50560
	ds_read_b128 v[132:135], v125 offset:51584
	ds_read_b128 v[136:139], v125 offset:52608
	s_waitcnt lgkmcnt(3)
	v_mfma_f32_16x16x32_bf16 v[140:143], v[48:51], v[108:111], v[56:59]
	s_waitcnt lgkmcnt(2)
	v_mfma_f32_16x16x32_bf16 v[96:99], v[48:51], v[128:131], v[96:99]
	s_waitcnt lgkmcnt(1)
	v_mfma_f32_16x16x32_bf16 v[84:87], v[48:51], v[132:135], v[84:87]
	s_waitcnt lgkmcnt(0)
	v_mfma_f32_16x16x32_bf16 v[76:79], v[48:51], v[136:139], v[76:79]
	ds_read_b128 v[48:51], v124 offset:34048
	s_waitcnt lgkmcnt(0)
	v_mfma_f32_16x16x32_bf16 v[72:75], v[48:51], v[108:111], v[72:75]
	ds_read_b128 v[56:59], v124 offset:35072
	v_mfma_f32_16x16x32_bf16 v[68:71], v[48:51], v[128:131], v[68:71]
	ds_read_b128 v[144:147], v124 offset:36096
	v_mfma_f32_16x16x32_bf16 v[60:63], v[48:51], v[132:135], v[60:63]
	ds_read_b128 v[148:151], v124 offset:41280
	v_mfma_f32_16x16x32_bf16 v[52:55], v[48:51], v[136:139], v[52:55]
	ds_read_b128 v[152:155], v124 offset:42304
	s_waitcnt lgkmcnt(3)
	v_mfma_f32_16x16x32_bf16 v[44:47], v[56:59], v[108:111], v[44:47]
	ds_read_b128 v[156:159], v124 offset:43328
	v_mfma_f32_16x16x32_bf16 v[40:43], v[56:59], v[128:131], v[40:43]
	ds_read_b128 v[48:51], v124 offset:44352
	v_mfma_f32_16x16x32_bf16 v[36:39], v[56:59], v[132:135], v[36:39]
	ds_read_b128 v[64:67], v125 offset:57792
	v_mfma_f32_16x16x32_bf16 v[28:31], v[56:59], v[136:139], v[28:31]
	ds_read_b128 v[104:107], v125 offset:58816
	s_waitcnt lgkmcnt(6)
	v_mfma_f32_16x16x32_bf16 v[92:95], v[144:147], v[108:111], v[92:95]
	ds_read_b128 v[112:115], v125 offset:59840
	v_mfma_f32_16x16x32_bf16 v[88:91], v[144:147], v[128:131], v[88:91]
	ds_read_b128 v[108:111], v125 offset:60864
	v_mfma_f32_16x16x32_bf16 v[80:83], v[144:147], v[132:135], v[80:83]
	v_mfma_f32_16x16x32_bf16 v[56:59], v[144:147], v[136:139], v[100:103]
	ds_write_b128 v126, v[32:35]
	s_waitcnt lgkmcnt(4)
	v_mfma_f32_16x16x32_bf16 v[100:103], v[148:151], v[64:67], v[140:143]
	s_waitcnt lgkmcnt(3)
	v_mfma_f32_16x16x32_bf16 v[96:99], v[148:151], v[104:107], v[96:99]
	ds_write_b128 v126, v[20:23] offset:2048
	s_waitcnt lgkmcnt(3)
	v_mfma_f32_16x16x32_bf16 v[84:87], v[148:151], v[112:115], v[84:87]
	s_waitcnt lgkmcnt(2)
	v_mfma_f32_16x16x32_bf16 v[76:79], v[148:151], v[108:111], v[76:79]
	ds_write_b128 v126, v[16:19] offset:4096
	v_mfma_f32_16x16x32_bf16 v[72:75], v[152:155], v[64:67], v[72:75]
	v_mfma_f32_16x16x32_bf16 v[68:71], v[152:155], v[104:107], v[68:71]
	ds_write_b128 v126, v[24:27] offset:6144
	v_mfma_f32_16x16x32_bf16 v[60:63], v[152:155], v[112:115], v[60:63]
	v_mfma_f32_16x16x32_bf16 v[52:55], v[152:155], v[108:111], v[52:55]
	ds_write_b128 v126, v[12:15] offset:16512
	v_mfma_f32_16x16x32_bf16 v[44:47], v[156:159], v[64:67], v[44:47]
	v_mfma_f32_16x16x32_bf16 v[40:43], v[156:159], v[104:107], v[40:43]
	ds_write_b128 v126, v[8:11] offset:18560
	v_mfma_f32_16x16x32_bf16 v[36:39], v[156:159], v[112:115], v[36:39]
	v_mfma_f32_16x16x32_bf16 v[28:31], v[156:159], v[108:111], v[28:31]
	ds_write_b128 v126, v[4:7] offset:20608
	ds_write_b128 v126, v[0:3] offset:22656
	s_cmp_lt_u32 s27, 14
	s_mov_b32 s5, s27
	s_waitcnt lgkmcnt(0)
	s_barrier
; #define MFMA16(a, b, c) __builtin_amdgcn_mfma_f32_16x16x32_bf16(a, b, c, 0, 0, 0)
; template <int WM, int WN, typename SrcF, typename PostF>
; __device__ __forceinline__ void gemm_stream(const int nsteps, SrcF src, PostF post, f32x4 (&acc)[WM][WN], char* smem) {
;     ...
;   acc[3][0] = MFMA16(pa, pb0, acc[3][0]);
;   acc[3][1] = MFMA16(pa, pb1, acc[3][1]);
;   acc[3][2] = MFMA16(pa, pb2, acc[3][2]);
;   acc[3][3] = MFMA16(pa, pb3, acc[3][3]);
; template <int WM, int WN>
; __device__ __forceinline__ void store_tile_bf16(const f32x4 (&acc)[WM][WN], u16* dst, int ld, char* smem) {
;     ...
; #pragma unroll
;   for (int m = 0; m < WM; ++m)
; #pragma unroll
;     for (int n = 0; n < WN; ++n)
; #pragma unroll
;       for (int j = 0; j < 4; ++j)
;         T[(wr * 16 * WM + m * 16 + fq * 4 + j) * STR + wc * 16 * WN + n * 16 + fr] = f2bf(acc[m][n][j]);
;   __syncthreads();
	s_waitcnt vmcnt(5)
	v_mov_b32_e32 v16, v232
	s_waitcnt vmcnt(0)
	v_mfma_f32_16x16x32_bf16 v[0:3], v[48:51], v[64:67], v[92:95]
	v_lshrrev_b32_e32 v18, 2, v16
	v_lshrrev_b32_e32 v17, 1, v16
	v_and_b32_e32 v18, 12, v18
	v_and_or_b32 v17, v17, s24, v18
	v_and_b32_e32 v18, 0x4f, v16
	v_mul_lo_u32 v17, v17, s26
	v_lshl_add_u32 v17, v18, 1, v17
	v_cvt_pk_bf16_f32 v18, 0, v101
	ds_write_b16_d16_hi v17, v18 offset:272
	v_cvt_pk_bf16_f32 v18, 0, v102
	ds_write_b16_d16_hi v17, v18 offset:544
	v_cvt_pk_bf16_f32 v18, 0, v103
	ds_write_b16_d16_hi v17, v18 offset:816
	v_cvt_pk_bf16_f32 v18, 0, v96
	ds_write_b16_d16_hi v17, v18 offset:32
	v_cvt_pk_bf16_f32 v18, 0, v97
	ds_write_b16_d16_hi v17, v18 offset:304
	v_cvt_pk_bf16_f32 v18, 0, v98
	ds_write_b16_d16_hi v17, v18 offset:576
	v_cvt_pk_bf16_f32 v18, 0, v99
	ds_write_b16_d16_hi v17, v18 offset:848
	v_cvt_pk_bf16_f32 v18, 0, v84
	ds_write_b16_d16_hi v17, v18 offset:64
	v_cvt_pk_bf16_f32 v18, 0, v85
	ds_write_b16_d16_hi v17, v18 offset:336
	v_cvt_pk_bf16_f32 v18, 0, v86
	ds_write_b16_d16_hi v17, v18 offset:608
	v_cvt_pk_bf16_f32 v18, 0, v87
	ds_write_b16_d16_hi v17, v18 offset:880
	v_cvt_pk_bf16_f32 v18, 0, v76
	ds_write_b16_d16_hi v17, v18 offset:96
	v_cvt_pk_bf16_f32 v18, 0, v77
	ds_write_b16_d16_hi v17, v18 offset:368
	v_cvt_pk_bf16_f32 v18, 0, v78
	ds_write_b16_d16_hi v17, v18 offset:640
	v_cvt_pk_bf16_f32 v18, 0, v79
	ds_write_b16_d16_hi v17, v18 offset:912
	v_cvt_pk_bf16_f32 v18, 0, v72
	ds_write_b16_d16_hi v17, v18 offset:4352
	v_cvt_pk_bf16_f32 v18, 0, v73
	ds_write_b16_d16_hi v17, v18 offset:4624
	v_cvt_pk_bf16_f32 v18, 0, v74
	ds_write_b16_d16_hi v17, v18 offset:4896
	v_cvt_pk_bf16_f32 v18, 0, v75
	ds_write_b16_d16_hi v17, v18 offset:5168
	v_cvt_pk_bf16_f32 v18, 0, v68
	ds_write_b16_d16_hi v17, v18 offset:4384
	v_cvt_pk_bf16_f32 v18, 0, v69
	ds_write_b16_d16_hi v17, v18 offset:4656
	v_cvt_pk_bf16_f32 v18, 0, v70
	ds_write_b16_d16_hi v17, v18 offset:4928
	v_cvt_pk_bf16_f32 v18, 0, v71
	ds_write_b16_d16_hi v17, v18 offset:5200
	v_cvt_pk_bf16_f32 v18, 0, v60
	ds_write_b16_d16_hi v17, v18 offset:4416
	v_cvt_pk_bf16_f32 v18, 0, v61
	ds_write_b16_d16_hi v17, v18 offset:4688
	v_cvt_pk_bf16_f32 v18, 0, v62
	ds_write_b16_d16_hi v17, v18 offset:4960
	v_cvt_pk_bf16_f32 v18, 0, v63
	ds_write_b16_d16_hi v17, v18 offset:5232
	v_cvt_pk_bf16_f32 v18, 0, v52
	ds_write_b16_d16_hi v17, v18 offset:4448
	v_cvt_pk_bf16_f32 v18, 0, v53
	ds_write_b16_d16_hi v17, v18 offset:4720
	v_cvt_pk_bf16_f32 v18, 0, v54
	ds_write_b16_d16_hi v17, v18 offset:4992
	v_cvt_pk_bf16_f32 v18, 0, v55
	ds_write_b16_d16_hi v17, v18 offset:5264
	v_cvt_pk_bf16_f32 v18, 0, v44
	ds_write_b16_d16_hi v17, v18 offset:8704
	v_cvt_pk_bf16_f32 v18, 0, v45
	ds_write_b16_d16_hi v17, v18 offset:8976
	v_cvt_pk_bf16_f32 v18, 0, v46
	ds_write_b16_d16_hi v17, v18 offset:9248
	v_cvt_pk_bf16_f32 v18, 0, v47
	ds_write_b16_d16_hi v17, v18 offset:9520
	v_cvt_pk_bf16_f32 v18, 0, v40
	ds_write_b16_d16_hi v17, v18 offset:8736
	v_cvt_pk_bf16_f32 v18, 0, v41
	ds_write_b16_d16_hi v17, v18 offset:9008
	v_cvt_pk_bf16_f32 v18, 0, v42
	ds_write_b16_d16_hi v17, v18 offset:9280
	v_cvt_pk_bf16_f32 v18, 0, v43
	ds_write_b16_d16_hi v17, v18 offset:9552
	v_cvt_pk_bf16_f32 v18, 0, v36
	ds_write_b16_d16_hi v17, v18 offset:8768
	v_cvt_pk_bf16_f32 v18, 0, v37
	ds_write_b16_d16_hi v17, v18 offset:9040
	v_cvt_pk_bf16_f32 v18, 0, v38
	ds_write_b16_d16_hi v17, v18 offset:9312
	v_cvt_pk_bf16_f32 v18, 0, v39
	ds_write_b16_d16_hi v17, v18 offset:9584
	v_cvt_pk_bf16_f32 v18, 0, v28
	ds_write_b16_d16_hi v17, v18 offset:8800
	v_cvt_pk_bf16_f32 v18, 0, v29
	ds_write_b16_d16_hi v17, v18 offset:9072
	v_cvt_pk_bf16_f32 v18, 0, v30
	ds_write_b16_d16_hi v17, v18 offset:9344
	v_cvt_pk_bf16_f32 v18, 0, v31
	ds_write_b16_d16_hi v17, v18 offset:9616
	v_cvt_pk_bf16_f32 v0, 0, v0
	ds_write_b16_d16_hi v17, v0 offset:13056
	v_cvt_pk_bf16_f32 v0, 0, v1
	v_mfma_f32_16x16x32_bf16 v[4:7], v[48:51], v[104:107], v[88:91]
	ds_write_b16_d16_hi v17, v0 offset:13328
	v_cvt_pk_bf16_f32 v0, 0, v2
	ds_write_b16_d16_hi v17, v0 offset:13600
	v_cvt_pk_bf16_f32 v0, 0, v3
	ds_write_b16_d16_hi v17, v0 offset:13872
	s_nop 0
	s_nop 1
	v_cvt_pk_bf16_f32 v0, 0, v4
	ds_write_b16_d16_hi v17, v0 offset:13088
	v_cvt_pk_bf16_f32 v0, 0, v5
	v_mfma_f32_16x16x32_bf16 v[8:11], v[48:51], v[112:115], v[80:83]
	ds_write_b16_d16_hi v17, v0 offset:13360
	v_cvt_pk_bf16_f32 v0, 0, v6
	ds_write_b16_d16_hi v17, v0 offset:13632
	v_cvt_pk_bf16_f32 v0, 0, v7
	ds_write_b16_d16_hi v17, v0 offset:13904
	s_nop 0
	s_nop 1
	v_cvt_pk_bf16_f32 v0, 0, v8
	ds_write_b16_d16_hi v17, v0 offset:13120
	v_cvt_pk_bf16_f32 v0, 0, v9
	v_mfma_f32_16x16x32_bf16 v[12:15], v[48:51], v[108:111], v[56:59]
	ds_write_b16_d16_hi v17, v0 offset:13392
	v_cvt_pk_bf16_f32 v0, 0, v10
	ds_write_b16_d16_hi v17, v0 offset:13664
	v_cvt_pk_bf16_f32 v0, 0, v11
	ds_write_b16_d16_hi v17, v0 offset:13936
	s_nop 0
	s_nop 1
	v_cvt_pk_bf16_f32 v0, 0, v12
	ds_write_b16_d16_hi v17, v0 offset:13152
	v_cvt_pk_bf16_f32 v0, 0, v13
	ds_write_b16_d16_hi v17, v0 offset:13424
	v_cvt_pk_bf16_f32 v0, 0, v14
	ds_write_b16_d16_hi v17, v0 offset:13696
	s_lshl_b64 s[6:7], s[6:7], 1
	v_cvt_pk_bf16_f32 v0, 0, v15
	s_add_u32 s6, s16, s6
	ds_write_b16_d16_hi v17, v0 offset:13968
	v_ashrrev_i32_e32 v0, 31, v16
	s_addc_u32 s7, s17, s7
	s_lshl_b32 s4, s4, 7
	v_lshrrev_b32_e32 v0, 28, v0
	s_ashr_i32 s5, s4, 31
	v_add_u32_e32 v0, v16, v0
	s_lshl_b64 s[4:5], s[4:5], 1
	v_ashrrev_i32_e32 v4, 4, v0
	v_and_b32_e32 v0, -16, v0
	s_add_u32 s4, s6, s4
	v_sub_u32_e32 v0, v16, v0
	v_ashrrev_i32_e32 v5, 31, v4
	s_addc_u32 s5, s7, s5
	v_mul_lo_u32 v1, v4, s26
	v_lshlrev_b32_e32 v6, 3, v0
	v_lshlrev_b64 v[4:5], 11, v[4:5]
	v_ashrrev_i32_e32 v7, 31, v6
	v_lshl_add_u64 v[4:5], s[4:5], 0, v[4:5]
	v_lshl_add_u64 v[8:9], v[6:7], 1, v[4:5]
	v_add_u32_e32 v4, 0x100, v16
	v_ashrrev_i32_e32 v5, 31, v4
	v_cvt_pk_bf16_f32 v19, 0, v100
	v_lshl_add_u32 v0, v0, 4, v1
	v_lshrrev_b32_e32 v5, 28, v5
	ds_write_b16_d16_hi v17, v19
	s_waitcnt lgkmcnt(0)
	s_barrier
; template <int WM, int WN>
; __device__ __forceinline__ void store_tile_bf16(const f32x4 (&acc)[WM][WN], u16* dst, int ld, char* smem) {
;     ...
;   constexpr int CPR = BN / 8;
; #pragma unroll
;   for (int i = 0; i < BM * CPR / 256; ++i) {
;     int q = tid + 256 * i, row = q / CPR, c = q % CPR;
;     uint4 v = *reinterpret_cast<const uint4*>(T + row * STR + c * 8);
;     *reinterpret_cast<uint4*>(dst + (size_t)row * ld + c * 8) = v;
;   }
	ds_read_b128 v[0:3], v0
	v_add_u32_e32 v5, v4, v5
	v_ashrrev_i32_e32 v10, 4, v5
	v_and_b32_e32 v5, -16, v5
	v_sub_u32_e32 v11, v4, v5
	v_mul_lo_u32 v4, v10, s26
	v_lshl_add_u32 v4, v11, 4, v4
	ds_read_b128 v[4:7], v4
	s_waitcnt lgkmcnt(1)
	global_store_dwordx4 v[8:9], v[0:3], off
	s_add_i32 s60, s60, s61
	s_cmp_lt_i32 s60, s62
	v_lshlrev_b32_e32 v0, 3, v11
	v_ashrrev_i32_e32 v11, 31, v10
	v_lshlrev_b64 v[2:3], 11, v[10:11]
	v_ashrrev_i32_e32 v1, 31, v0
	v_lshl_add_u64 v[2:3], s[4:5], 0, v[2:3]
	v_lshl_add_u64 v[0:1], v[0:1], 1, v[2:3]
	s_waitcnt lgkmcnt(0)
	global_store_dwordx4 v[0:1], v[4:7], off
	v_add_u32_e32 v0, 0x200, v16
	v_ashrrev_i32_e32 v1, 31, v0
	v_lshrrev_b32_e32 v1, 28, v1
	v_add_u32_e32 v1, v0, v1
	v_ashrrev_i32_e32 v4, 4, v1
	v_and_b32_e32 v1, -16, v1
	v_sub_u32_e32 v0, v0, v1
	v_ashrrev_i32_e32 v5, 31, v4
	v_mul_lo_u32 v1, v4, s26
	v_lshlrev_b32_e32 v6, 3, v0
	v_lshlrev_b64 v[4:5], 11, v[4:5]
	v_ashrrev_i32_e32 v7, 31, v6
	v_lshl_add_u64 v[4:5], s[4:5], 0, v[4:5]
	v_lshl_add_u64 v[8:9], v[6:7], 1, v[4:5]
	v_add_u32_e32 v4, 0x300, v16
	v_ashrrev_i32_e32 v5, 31, v4
	v_lshl_add_u32 v0, v0, 4, v1
	v_lshrrev_b32_e32 v5, 28, v5
	ds_read_b128 v[0:3], v0
	v_add_u32_e32 v5, v4, v5
	v_ashrrev_i32_e32 v10, 4, v5
	v_and_b32_e32 v5, -16, v5
	v_sub_u32_e32 v11, v4, v5
	v_mul_lo_u32 v4, v10, s26
	v_lshl_add_u32 v4, v11, 4, v4
	ds_read_b128 v[4:7], v4
	s_waitcnt lgkmcnt(1)
	global_store_dwordx4 v[8:9], v[0:3], off
	s_nop 1
	v_lshlrev_b32_e32 v0, 3, v11
	v_ashrrev_i32_e32 v11, 31, v10
	v_lshlrev_b64 v[2:3], 11, v[10:11]
	v_ashrrev_i32_e32 v1, 31, v0
	v_lshl_add_u64 v[2:3], s[4:5], 0, v[2:3]
	v_lshl_add_u64 v[0:1], v[0:1], 1, v[2:3]
	s_waitcnt lgkmcnt(0)
	global_store_dwordx4 v[0:1], v[4:7], off
	v_add_u32_e32 v0, 0x400, v16
	v_ashrrev_i32_e32 v1, 31, v0
	v_lshrrev_b32_e32 v1, 28, v1
	v_add_u32_e32 v1, v0, v1
	v_ashrrev_i32_e32 v4, 4, v1
	v_and_b32_e32 v1, -16, v1
	v_sub_u32_e32 v0, v0, v1
	v_ashrrev_i32_e32 v5, 31, v4
	v_mul_lo_u32 v1, v4, s26
	v_lshlrev_b32_e32 v6, 3, v0
	v_lshlrev_b64 v[4:5], 11, v[4:5]
	v_ashrrev_i32_e32 v7, 31, v6
	v_lshl_add_u64 v[4:5], s[4:5], 0, v[4:5]
	v_lshl_add_u64 v[8:9], v[6:7], 1, v[4:5]
	v_add_u32_e32 v4, 0x500, v16
	v_ashrrev_i32_e32 v5, 31, v4
	v_lshl_add_u32 v0, v0, 4, v1
	v_lshrrev_b32_e32 v5, 28, v5
	ds_read_b128 v[0:3], v0
	v_add_u32_e32 v5, v4, v5
	v_ashrrev_i32_e32 v10, 4, v5
	v_and_b32_e32 v5, -16, v5
	v_sub_u32_e32 v11, v4, v5
	v_mul_lo_u32 v4, v10, s26
	v_lshl_add_u32 v4, v11, 4, v4
	ds_read_b128 v[4:7], v4
	s_waitcnt lgkmcnt(1)
	global_store_dwordx4 v[8:9], v[0:3], off
	s_nop 1
	v_lshlrev_b32_e32 v0, 3, v11
	v_ashrrev_i32_e32 v11, 31, v10
	v_lshlrev_b64 v[2:3], 11, v[10:11]
	v_ashrrev_i32_e32 v1, 31, v0
	v_lshl_add_u64 v[2:3], s[4:5], 0, v[2:3]
	v_lshl_add_u64 v[0:1], v[0:1], 1, v[2:3]
	s_waitcnt lgkmcnt(0)
	global_store_dwordx4 v[0:1], v[4:7], off
	v_add_u32_e32 v0, 0x600, v16
	v_ashrrev_i32_e32 v1, 31, v0
	v_lshrrev_b32_e32 v1, 28, v1
	v_add_u32_e32 v1, v0, v1
	v_ashrrev_i32_e32 v4, 4, v1
	v_and_b32_e32 v1, -16, v1
	v_sub_u32_e32 v0, v0, v1
	v_ashrrev_i32_e32 v5, 31, v4
	v_mul_lo_u32 v1, v4, s26
	v_lshlrev_b32_e32 v6, 3, v0
	v_lshlrev_b64 v[4:5], 11, v[4:5]
	v_ashrrev_i32_e32 v7, 31, v6
	v_lshl_add_u64 v[4:5], s[4:5], 0, v[4:5]
	v_lshl_add_u64 v[8:9], v[6:7], 1, v[4:5]
	v_add_u32_e32 v4, 0x700, v16
	v_ashrrev_i32_e32 v5, 31, v4
	v_lshl_add_u32 v0, v0, 4, v1
	v_lshrrev_b32_e32 v5, 28, v5
	ds_read_b128 v[0:3], v0
	v_add_u32_e32 v5, v4, v5
	v_ashrrev_i32_e32 v10, 4, v5
	v_and_b32_e32 v5, -16, v5
	v_sub_u32_e32 v11, v4, v5
	v_mul_lo_u32 v4, v10, s26
	v_lshl_add_u32 v4, v11, 4, v4
	ds_read_b128 v[4:7], v4
	s_waitcnt lgkmcnt(1)
	global_store_dwordx4 v[8:9], v[0:3], off
	s_nop 1
	v_lshlrev_b32_e32 v0, 3, v11
	v_ashrrev_i32_e32 v11, 31, v10
	v_lshlrev_b64 v[2:3], 11, v[10:11]
	v_ashrrev_i32_e32 v1, 31, v0
	v_lshl_add_u64 v[2:3], s[4:5], 0, v[2:3]
	v_lshl_add_u64 v[0:1], v[0:1], 1, v[2:3]
	s_waitcnt lgkmcnt(0)
	global_store_dwordx4 v[0:1], v[4:7], off
	s_cbranch_scc1 .LBB0_1280

; __device__ __forceinline__ float bflo(unsigned w) { return __uint_as_float(w << 16); }
; __device__ __forceinline__ float bfhi(unsigned w) { return __uint_as_float(w & 0xffff0000u); }
; __device__ void norm_phase(const Params& p, int layer) {
;     ...
;   for (int r2 = gw; r2 < NTOK / 2; r2 += nw) {
;     const int row = r2 * 2 + sub;
;     const size_t rbase = (size_t)row * DM + l32 * 4;
;     float4 xv[8];
;     if (layer < 0) {
; #pragma unroll
;       for (int i = 0; i < 8; ++i) xv[i] = *reinterpret_cast<const float4*>(p.x + rbase + i * 128);
;     } else {
;       const float* xr = (layer == 0) ? p.x : p.out;
;       float4 ov[8];
;       float ss = 0.f;
; #pragma unroll
;       for (int i = 0; i < 8; ++i) {
;         {
;           uint2 ob = *reinterpret_cast<const uint2*>(OUTB + rbase + i * 128);
;           ov[i] = make_float4(bflo(ob.x), bfhi(ob.x), bflo(ob.y), bfhi(ob.y));
;         }
;         xv[i] = *reinterpret_cast<const float4*>(xr + rbase + i * 128);
;       }
; #pragma unroll
;       for (int i = 0; i < 8; ++i) ss += ov[i].x * ov[i].x + ov[i].y * ov[i].y + ov[i].z * ov[i].z + ov[i].w * ov[i].w;
;       ss = half_wave_sum(ss);
.LBB0_1322:
	v_ashrrev_i32_e32 v5, 31, v4
	v_lshlrev_b64 v[6:7], 10, v[4:5]
	v_or_b32_e32 v6, v6, v0
	v_lshl_add_u64 v[18:19], v[6:7], 1, s[0:1]
	global_load_dwordx2 v[22:23], v[18:19], off
	global_load_dwordx2 v[24:25], v[18:19], off offset:256
	global_load_dwordx2 v[26:27], v[18:19], off offset:512
	global_load_dwordx2 v[28:29], v[18:19], off offset:768
	global_load_dwordx2 v[30:31], v[18:19], off offset:1024
	global_load_dwordx2 v[32:33], v[18:19], off offset:1280
	global_load_dwordx2 v[34:35], v[18:19], off offset:1536
	global_load_dwordx2 v[36:37], v[18:19], off offset:1792
	global_load_dwordx4 v[14:17], v[2:3], off
	v_lshl_add_u64 v[6:7], v[6:7], 2, s[6:7]
	global_load_dwordx4 v[18:21], v[6:7], off
	v_add_u32_e32 v1, s56, v1
	v_add_u32_e32 v4, s4, v4
	s_waitcnt vmcnt(9)
	v_lshlrev_b32_e32 v38, 16, v22
	v_and_b32_e32 v39, 0xffff0000, v22
	s_waitcnt vmcnt(8)
	v_lshlrev_b32_e32 v42, 16, v24
	v_and_b32_e32 v43, 0xffff0000, v24
	s_waitcnt vmcnt(7)
	v_and_b32_e32 v47, 0xffff0000, v26
	s_waitcnt vmcnt(6)
	v_and_b32_e32 v49, 0xffff0000, v28
	v_lshlrev_b32_e32 v40, 16, v23
	v_and_b32_e32 v41, 0xffff0000, v23
	v_lshlrev_b32_e32 v44, 16, v25
	v_and_b32_e32 v45, 0xffff0000, v25
	v_lshlrev_b32_e32 v46, 16, v26
	v_lshlrev_b32_e32 v48, 16, v28
	v_pk_mul_f32 v[22:23], v[38:39], v[38:39]
	v_pk_mul_f32 v[58:59], v[42:43], v[42:43]
	v_mov_b32_e32 v64, v47
	v_mov_b32_e32 v65, v49
	v_lshlrev_b32_e32 v26, 16, v27
	v_lshlrev_b32_e32 v28, 16, v29
	s_waitcnt vmcnt(5)
	v_and_b32_e32 v51, 0xffff0000, v30
	s_waitcnt vmcnt(4)
	v_and_b32_e32 v53, 0xffff0000, v32
	v_pk_mul_f32 v[24:25], v[40:41], v[40:41]
	v_pk_mul_f32 v[60:61], v[44:45], v[44:45]
	v_mov_b32_e32 v62, v46
	v_mov_b32_e32 v63, v48
	v_pk_mul_f32 v[64:65], v[64:65], v[64:65]
	v_add_f32_e32 v5, v58, v59
	v_add_f32_e32 v22, v22, v23
	v_and_b32_e32 v27, 0xffff0000, v27
	v_and_b32_e32 v29, 0xffff0000, v29
	v_lshlrev_b32_e32 v50, 16, v30
	v_lshlrev_b32_e32 v52, 16, v32
	v_mov_b32_e32 v66, v26
	v_mov_b32_e32 v67, v28
	v_mov_b32_e32 v72, v51
	v_mov_b32_e32 v73, v53
	v_pk_fma_f32 v[58:59], v[62:63], v[62:63], v[64:65]
	v_add_f32_e32 v5, v5, v60
	v_add_f32_e32 v22, v22, v24
	v_lshlrev_b32_e32 v30, 16, v31
	v_lshlrev_b32_e32 v32, 16, v33
	s_waitcnt vmcnt(3)
	v_and_b32_e32 v55, 0xffff0000, v34
	s_waitcnt vmcnt(2)
	v_and_b32_e32 v57, 0xffff0000, v36
	v_mov_b32_e32 v68, v27
	v_mov_b32_e32 v69, v29
	v_mov_b32_e32 v70, v50
	v_mov_b32_e32 v71, v52
	v_pk_mul_f32 v[72:73], v[72:73], v[72:73]
	v_pk_fma_f32 v[58:59], v[66:67], v[66:67], v[58:59]
	v_add_f32_e32 v5, v61, v5
	v_add_f32_e32 v22, v25, v22
	v_and_b32_e32 v31, 0xffff0000, v31
	v_and_b32_e32 v33, 0xffff0000, v33
	v_lshlrev_b32_e32 v54, 16, v34
	v_lshlrev_b32_e32 v56, 16, v36
	v_mov_b32_e32 v74, v30
	v_mov_b32_e32 v75, v32
	v_mov_b32_e32 v80, v55
	v_mov_b32_e32 v81, v57
	v_pk_fma_f32 v[62:63], v[70:71], v[70:71], v[72:73]
	v_pk_fma_f32 v[58:59], v[68:69], v[68:69], v[58:59]
	v_add_f32_e32 v5, v22, v5
	v_lshlrev_b32_e32 v34, 16, v35
	v_lshlrev_b32_e32 v36, 16, v37
	v_mov_b32_e32 v76, v31
	v_mov_b32_e32 v77, v33
	v_mov_b32_e32 v78, v54
	v_mov_b32_e32 v79, v56
	v_pk_mul_f32 v[80:81], v[80:81], v[80:81]
	v_pk_fma_f32 v[62:63], v[74:75], v[74:75], v[62:63]
	v_add_f32_e32 v5, v5, v58
	v_and_b32_e32 v35, 0xffff0000, v35
	v_and_b32_e32 v37, 0xffff0000, v37
	v_mov_b32_e32 v82, v34
	v_mov_b32_e32 v83, v36
	v_pk_fma_f32 v[64:65], v[78:79], v[78:79], v[80:81]
	v_pk_fma_f32 v[60:61], v[76:77], v[76:77], v[62:63]
	v_add_f32_e32 v5, v5, v59
	v_mov_b32_e32 v84, v35
	v_mov_b32_e32 v85, v37
	v_pk_fma_f32 v[64:65], v[82:83], v[82:83], v[64:65]
	v_add_f32_e32 v5, v5, v60
	v_pk_fma_f32 v[62:63], v[84:85], v[84:85], v[64:65]
	v_add_f32_e32 v5, v5, v61
	v_add_f32_e32 v5, v5, v62
	v_add_f32_e32 v5, v5, v63
	ds_bpermute_b32 v22, v8, v5
	s_waitcnt lgkmcnt(0)
	v_add_f32_e32 v5, v5, v22
	ds_bpermute_b32 v22, v9, v5
	s_waitcnt lgkmcnt(0)
; __device__ void norm_phase(const Params& p, int layer) {
;     ...
;       float rstd = rsqrtf(ss * (1.f / 1024.f) + 1e-6f);
; #pragma unroll
;       for (int i = 0; i < 8; ++i) {
;         float4 g = *reinterpret_cast<const float4*>(p.g_post + (size_t)layer * DM + l32 * 4 + i * 128);
;         xv[i].x += ov[i].x * rstd * g.x;
;         xv[i].y += ov[i].y * rstd * g.y;
;         xv[i].z += ov[i].z * rstd * g.z;
;         xv[i].w += ov[i].w * rstd * g.w;
;         *reinterpret_cast<float4*>(p.out + rbase + i * 128) = xv[i];
;       }
	v_add_f32_e32 v5, v5, v22
	ds_bpermute_b32 v22, v10, v5
	s_waitcnt lgkmcnt(0)
	v_add_f32_e32 v5, v5, v22
	ds_bpermute_b32 v22, v11, v5
	s_waitcnt lgkmcnt(0)
	v_add_f32_e32 v5, v5, v22
	ds_bpermute_b32 v22, v12, v5
	s_waitcnt lgkmcnt(0)
	v_add_f32_e32 v5, v5, v22
	v_fmamk_f32 v5, v5, 0x3a800000, v13
	v_mul_f32_e32 v22, 0x4b800000, v5
	v_cmp_gt_f32_e32 vcc, s5, v5
	s_nop 1
	v_cndmask_b32_e32 v5, v5, v22, vcc
	v_rsq_f32_e32 v5, v5
	global_load_dwordx4 v[22:25], v[6:7], off offset:512
	v_mul_f32_e32 v58, 0x45800000, v5
	v_cndmask_b32_e32 v58, v5, v58, vcc
	v_pk_mul_f32 v[38:39], v[58:59], v[38:39] op_sel_hi:[0,1]
	v_pk_mul_f32 v[40:41], v[58:59], v[40:41] op_sel_hi:[0,1]
	s_waitcnt vmcnt(1)
	v_pk_fma_f32 v[14:15], v[14:15], v[38:39], v[18:19]
	v_pk_fma_f32 v[16:17], v[16:17], v[40:41], v[20:21]
	global_store_dwordx4 v[6:7], v[14:17], off
	s_nop 0
	global_load_dwordx4 v[14:17], v[2:3], off offset:512
	v_pk_mul_f32 v[18:19], v[58:59], v[42:43] op_sel_hi:[0,1]
	v_pk_mul_f32 v[20:21], v[58:59], v[44:45] op_sel_hi:[0,1]
	v_pk_mul_f32 v[38:39], v[58:59], v[46:47] op_sel_hi:[0,1]
	v_pk_mul_f32 v[26:27], v[58:59], v[26:27] op_sel_hi:[0,1]
	v_cmp_lt_i32_e32 vcc, s8, v1
	s_or_b64 s[2:3], vcc, s[2:3]
	s_waitcnt vmcnt(0)
	v_pk_fma_f32 v[14:15], v[18:19], v[14:15], v[22:23]
	v_pk_fma_f32 v[16:17], v[20:21], v[16:17], v[24:25]
	global_store_dwordx4 v[6:7], v[14:17], off offset:512
	s_nop 0
	global_load_dwordx4 v[14:17], v[2:3], off offset:1024
	s_nop 0
	global_load_dwordx4 v[18:21], v[6:7], off offset:1024
	global_load_dwordx4 v[22:25], v[6:7], off offset:1536
	s_waitcnt vmcnt(1)
	v_pk_fma_f32 v[14:15], v[38:39], v[14:15], v[18:19]
	v_pk_fma_f32 v[16:17], v[26:27], v[16:17], v[20:21]
	global_store_dwordx4 v[6:7], v[14:17], off offset:1024
	s_nop 0
	global_load_dwordx4 v[14:17], v[2:3], off offset:1536
	v_pk_mul_f32 v[18:19], v[58:59], v[48:49] op_sel_hi:[0,1]
	v_pk_mul_f32 v[20:21], v[58:59], v[28:29] op_sel_hi:[0,1]
	v_pk_mul_f32 v[26:27], v[58:59], v[50:51] op_sel_hi:[0,1]
	v_pk_mul_f32 v[28:29], v[58:59], v[30:31] op_sel_hi:[0,1]
	s_waitcnt vmcnt(0)
	v_pk_fma_f32 v[14:15], v[18:19], v[14:15], v[22:23]
	v_pk_fma_f32 v[16:17], v[20:21], v[16:17], v[24:25]
	global_store_dwordx4 v[6:7], v[14:17], off offset:1536
	s_nop 0
	global_load_dwordx4 v[14:17], v[2:3], off offset:2048
	s_nop 0
	global_load_dwordx4 v[18:21], v[6:7], off offset:2048
	global_load_dwordx4 v[22:25], v[6:7], off offset:2560
	s_waitcnt vmcnt(1)
	v_pk_fma_f32 v[14:15], v[26:27], v[14:15], v[18:19]
	v_pk_fma_f32 v[16:17], v[28:29], v[16:17], v[20:21]
	global_store_dwordx4 v[6:7], v[14:17], off offset:2048
	s_nop 0
	global_load_dwordx4 v[14:17], v[2:3], off offset:2560
	v_pk_mul_f32 v[18:19], v[58:59], v[52:53] op_sel_hi:[0,1]
	v_pk_mul_f32 v[20:21], v[58:59], v[32:33] op_sel_hi:[0,1]
	v_pk_mul_f32 v[26:27], v[58:59], v[54:55] op_sel_hi:[0,1]
	v_pk_mul_f32 v[28:29], v[58:59], v[34:35] op_sel_hi:[0,1]
	s_waitcnt vmcnt(0)
	v_pk_fma_f32 v[14:15], v[18:19], v[14:15], v[22:23]
	v_pk_fma_f32 v[16:17], v[20:21], v[16:17], v[24:25]
	global_store_dwordx4 v[6:7], v[14:17], off offset:2560
	s_nop 0
	global_load_dwordx4 v[14:17], v[2:3], off offset:3072
	s_nop 0
	global_load_dwordx4 v[18:21], v[6:7], off offset:3072
	global_load_dwordx4 v[22:25], v[6:7], off offset:3584
	s_waitcnt vmcnt(1)
	v_pk_fma_f32 v[14:15], v[26:27], v[14:15], v[18:19]
	v_pk_fma_f32 v[16:17], v[28:29], v[16:17], v[20:21]
	global_store_dwordx4 v[6:7], v[14:17], off offset:3072
	s_nop 0
	global_load_dwordx4 v[14:17], v[2:3], off offset:3584
	v_pk_mul_f32 v[18:19], v[58:59], v[56:57] op_sel_hi:[0,1]
	v_pk_mul_f32 v[20:21], v[58:59], v[36:37] op_sel_hi:[0,1]
	s_waitcnt vmcnt(0)
	v_pk_fma_f32 v[14:15], v[18:19], v[14:15], v[22:23]
	v_pk_fma_f32 v[16:17], v[20:21], v[16:17], v[24:25]
	global_store_dwordx4 v[6:7], v[14:17], off offset:3584
	s_andn2_b64 exec, exec, s[2:3]
	s_cbranch_execnz .LBB0_1322
